# lane-permutation moves folded into the consuming max/add as DPP operands; s_nop fillers that no wait-state rule needs removed (hazard rows checked per nop)
# speedup vs baseline: 1.0129x; 1.0089x over previous
.LBB0_5:
	s_or_b64 exec, exec, s[6:7]
	s_load_dwordx16 s[72:87], s[0:1], 0x0
	s_load_dwordx16 s[16:31], s[0:1], 0x40
	s_cmp_lg_u64 s[92:93], 0
	s_waitcnt lgkmcnt(0)
	v_writelane_b32 v251, s16, 4
	s_nop 1
	v_writelane_b32 v251, s17, 5
	v_writelane_b32 v251, s18, 6
	v_writelane_b32 v251, s19, 7
	v_writelane_b32 v251, s20, 8
	v_writelane_b32 v251, s21, 9
	v_writelane_b32 v251, s22, 10
	v_writelane_b32 v251, s23, 11
	v_writelane_b32 v251, s24, 12
	v_writelane_b32 v251, s25, 13
	v_writelane_b32 v251, s26, 14
	v_writelane_b32 v251, s27, 15
	v_writelane_b32 v251, s28, 16
	v_writelane_b32 v251, s29, 17
	v_writelane_b32 v251, s30, 18
	v_writelane_b32 v251, s31, 19
	s_load_dwordx16 s[16:31], s[0:1], 0x80
	s_waitcnt lgkmcnt(0)
	v_writelane_b32 v251, s16, 20
	v_writelane_b32 v251, s17, 21
	v_writelane_b32 v251, s18, 22
	v_writelane_b32 v251, s19, 23
	v_writelane_b32 v251, s20, 24
	v_writelane_b32 v251, s21, 25
	v_writelane_b32 v251, s22, 26
	v_writelane_b32 v251, s23, 27
	v_writelane_b32 v251, s24, 28
	v_writelane_b32 v251, s25, 29
	v_writelane_b32 v251, s26, 30
	v_writelane_b32 v251, s27, 31
	v_writelane_b32 v251, s28, 32
	v_writelane_b32 v251, s29, 33
	v_writelane_b32 v251, s30, 34
	v_writelane_b32 v251, s31, 35
	s_cbranch_scc0 .LBB0_7
	s_cmpk_gt_i32 s2, 0x1c1f
	s_cbranch_scc0 .LBB0_18
	s_branch .LBB0_89

.LBB0_84:
	v_lshl_add_u64 v[108:109], v[136:137], 0, s[40:41]
	ds_read_b128 v[68:71], v142
	ds_read_b128 v[0:3], v142 offset:16
	ds_read_b128 v[72:75], v142 offset:4096
	ds_read_b128 v[64:67], v142 offset:8192
	ds_read_b128 v[60:63], v142 offset:12288
	ds_read_b128 v[20:23], v142 offset:16384
	ds_read_b128 v[16:19], v142 offset:20480
	ds_read_b128 v[12:15], v142 offset:24576
	ds_read_b128 v[8:11], v142 offset:28672
	ds_read_b128 v[4:7], v142 offset:32768
	ds_read_b128 v[76:79], v142 offset:4112
	ds_read_b128 v[80:83], v142 offset:8208
	ds_read_b128 v[84:87], v142 offset:12304
	ds_read_b128 v[88:91], v142 offset:16400
	ds_read_b128 v[92:95], v142 offset:20496
	ds_read_b128 v[96:99], v142 offset:24592
	ds_read_b128 v[100:103], v142 offset:28688
	ds_read_b128 v[104:107], v142 offset:32784
	global_load_dwordx4 v[144:147], v[108:109], off
	s_mov_b32 s0, 0x12000
	s_mov_b32 s6, 0x1b000
	s_mov_b32 s8, 0x24000
	s_mov_b32 s10, 0x2d000
	s_mov_b32 s12, 0x36000
	s_mov_b32 s14, 0x3f000
	v_add_co_u32_e32 v110, vcc, s51, v108
	v_add_co_u32_e64 v112, s[0:1], s0, v108
	v_add_co_u32_e64 v114, s[6:7], s6, v108
	v_add_co_u32_e64 v116, s[8:9], s8, v108
	v_add_co_u32_e64 v118, s[10:11], s10, v108
	v_add_co_u32_e64 v152, s[12:13], s12, v108
	v_add_co_u32_e64 v108, s[14:15], s14, v108
	v_addc_co_u32_e32 v111, vcc, 0, v109, vcc
	v_addc_co_u32_e64 v113, vcc, 0, v109, s[0:1]
	v_addc_co_u32_e64 v115, vcc, 0, v109, s[6:7]
	v_addc_co_u32_e64 v117, vcc, 0, v109, s[8:9]
	v_addc_co_u32_e64 v119, vcc, 0, v109, s[10:11]
	v_addc_co_u32_e64 v153, vcc, 0, v109, s[12:13]
	v_addc_co_u32_e64 v109, vcc, 0, v109, s[14:15]
	global_load_dwordx4 v[148:151], v[110:111], off
	global_load_dwordx4 v[128:131], v[112:113], off
	global_load_dwordx4 v[124:127], v[114:115], off
	global_load_dwordx4 v[120:123], v[116:117], off
	global_load_dwordx4 v[116:119], v[118:119], off
	global_load_dwordx4 v[112:115], v[152:153], off
	global_load_dwordx4 v[108:111], v[108:109], off
	s_waitcnt lgkmcnt(14)
	v_mov_b32_e32 v152, v71
	v_mov_b32_e32 v154, v75
	v_mov_b32_e32 v156, v67
	s_waitcnt lgkmcnt(13)
	v_mov_b32_e32 v158, v63
	s_waitcnt lgkmcnt(12)
	v_mov_b32_e32 v138, v23
	s_waitcnt lgkmcnt(11)
	v_mov_b32_e32 v132, v19
	s_waitcnt lgkmcnt(8)
	v_mov_b32_e32 v160, v7
	s_add_u32 s40, s40, 0x48000
	s_addc_u32 s41, s41, 0
	v_add_u32_e32 v142, 32, v142
	s_cmp_eq_u32 s40, 0x240000
	s_waitcnt vmcnt(7)
	v_pk_fma_f32 v[44:45], v[144:145], v[68:69], v[44:45] op_sel_hi:[1,0,1]
	v_pk_fma_f32 v[46:47], v[146:147], v[68:69], v[46:47] op_sel_hi:[1,0,1]
	v_pk_fma_f32 v[56:57], v[144:145], v[72:73], v[56:57] op_sel_hi:[1,0,1]
	v_pk_fma_f32 v[58:59], v[146:147], v[72:73], v[58:59] op_sel_hi:[1,0,1]
	v_pk_fma_f32 v[52:53], v[144:145], v[64:65], v[52:53] op_sel_hi:[1,0,1]
	v_pk_fma_f32 v[54:55], v[146:147], v[64:65], v[54:55] op_sel_hi:[1,0,1]
	v_pk_fma_f32 v[48:49], v[144:145], v[60:61], v[48:49] op_sel_hi:[1,0,1]
	v_pk_fma_f32 v[50:51], v[146:147], v[60:61], v[50:51] op_sel_hi:[1,0,1]
	v_pk_fma_f32 v[40:41], v[144:145], v[20:21], v[40:41] op_sel_hi:[1,0,1]
	v_pk_fma_f32 v[42:43], v[146:147], v[20:21], v[42:43] op_sel_hi:[1,0,1]
	v_pk_fma_f32 v[36:37], v[144:145], v[16:17], v[36:37] op_sel_hi:[1,0,1]
	v_pk_fma_f32 v[38:39], v[146:147], v[16:17], v[38:39] op_sel_hi:[1,0,1]
	v_pk_fma_f32 v[32:33], v[144:145], v[12:13], v[32:33] op_sel_hi:[1,0,1]
	v_pk_fma_f32 v[34:35], v[146:147], v[12:13], v[34:35] op_sel_hi:[1,0,1]
	v_pk_fma_f32 v[28:29], v[144:145], v[8:9], v[28:29] op_sel_hi:[1,0,1]
	v_pk_fma_f32 v[30:31], v[146:147], v[8:9], v[30:31] op_sel_hi:[1,0,1]
	v_pk_fma_f32 v[24:25], v[144:145], v[4:5], v[24:25] op_sel_hi:[1,0,1]
	v_pk_fma_f32 v[26:27], v[146:147], v[4:5], v[26:27] op_sel_hi:[1,0,1]
	v_mov_b32_e32 v144, v15
	v_mov_b32_e32 v146, v11
	s_waitcnt vmcnt(6)
	v_pk_fma_f32 v[44:45], v[148:149], v[68:69], v[44:45] op_sel:[0,1,0]
	v_pk_fma_f32 v[46:47], v[150:151], v[68:69], v[46:47] op_sel:[0,1,0]
	v_pk_fma_f32 v[56:57], v[148:149], v[72:73], v[56:57] op_sel:[0,1,0]
	v_pk_fma_f32 v[58:59], v[150:151], v[72:73], v[58:59] op_sel:[0,1,0]
	v_pk_fma_f32 v[52:53], v[148:149], v[64:65], v[52:53] op_sel:[0,1,0]
	v_pk_fma_f32 v[54:55], v[150:151], v[64:65], v[54:55] op_sel:[0,1,0]
	v_pk_fma_f32 v[48:49], v[148:149], v[60:61], v[48:49] op_sel:[0,1,0]
	v_pk_fma_f32 v[50:51], v[150:151], v[60:61], v[50:51] op_sel:[0,1,0]
	v_pk_fma_f32 v[40:41], v[148:149], v[20:21], v[40:41] op_sel:[0,1,0]
	v_pk_fma_f32 v[20:21], v[150:151], v[20:21], v[42:43] op_sel:[0,1,0]
	v_pk_fma_f32 v[36:37], v[148:149], v[16:17], v[36:37] op_sel:[0,1,0]
	v_pk_fma_f32 v[16:17], v[150:151], v[16:17], v[38:39] op_sel:[0,1,0]
	v_pk_fma_f32 v[32:33], v[148:149], v[12:13], v[32:33] op_sel:[0,1,0]
	v_pk_fma_f32 v[12:13], v[150:151], v[12:13], v[34:35] op_sel:[0,1,0]
	v_pk_fma_f32 v[28:29], v[148:149], v[8:9], v[28:29] op_sel:[0,1,0]
	v_pk_fma_f32 v[8:9], v[150:151], v[8:9], v[30:31] op_sel:[0,1,0]
	v_pk_fma_f32 v[24:25], v[148:149], v[4:5], v[24:25] op_sel:[0,1,0]
	v_pk_fma_f32 v[4:5], v[150:151], v[4:5], v[26:27] op_sel:[0,1,0]
	s_waitcnt vmcnt(5)
	v_pk_fma_f32 v[34:35], v[128:129], v[70:71], v[44:45] op_sel_hi:[1,0,1]
	v_pk_fma_f32 v[38:39], v[130:131], v[70:71], v[46:47] op_sel_hi:[1,0,1]
	v_pk_fma_f32 v[44:45], v[128:129], v[74:75], v[56:57] op_sel_hi:[1,0,1]
	v_pk_fma_f32 v[46:47], v[130:131], v[74:75], v[58:59] op_sel_hi:[1,0,1]
	v_pk_fma_f32 v[52:53], v[128:129], v[66:67], v[52:53] op_sel_hi:[1,0,1]
	v_pk_fma_f32 v[54:55], v[130:131], v[66:67], v[54:55] op_sel_hi:[1,0,1]
	v_pk_fma_f32 v[48:49], v[128:129], v[62:63], v[48:49] op_sel_hi:[1,0,1]
	v_pk_fma_f32 v[50:51], v[130:131], v[62:63], v[50:51] op_sel_hi:[1,0,1]
	v_pk_fma_f32 v[40:41], v[128:129], v[22:23], v[40:41] op_sel_hi:[1,0,1]
	v_pk_fma_f32 v[20:21], v[130:131], v[22:23], v[20:21] op_sel_hi:[1,0,1]
	v_pk_fma_f32 v[22:23], v[128:129], v[18:19], v[36:37] op_sel_hi:[1,0,1]
	v_pk_fma_f32 v[16:17], v[130:131], v[18:19], v[16:17] op_sel_hi:[1,0,1]
	v_pk_fma_f32 v[18:19], v[128:129], v[14:15], v[32:33] op_sel_hi:[1,0,1]
	v_pk_fma_f32 v[12:13], v[130:131], v[14:15], v[12:13] op_sel_hi:[1,0,1]
	v_pk_fma_f32 v[14:15], v[128:129], v[10:11], v[28:29] op_sel_hi:[1,0,1]
	v_pk_fma_f32 v[8:9], v[130:131], v[10:11], v[8:9] op_sel_hi:[1,0,1]
	v_pk_fma_f32 v[10:11], v[128:129], v[6:7], v[24:25] op_sel_hi:[1,0,1]
	v_pk_fma_f32 v[4:5], v[130:131], v[6:7], v[4:5] op_sel_hi:[1,0,1]
	s_waitcnt vmcnt(4)
	v_pk_fma_f32 v[6:7], v[124:125], v[152:153], v[34:35] op_sel_hi:[1,0,1]
	v_pk_fma_f32 v[24:25], v[126:127], v[152:153], v[38:39] op_sel_hi:[1,0,1]
	v_pk_fma_f32 v[28:29], v[124:125], v[154:155], v[44:45] op_sel_hi:[1,0,1]
	v_pk_fma_f32 v[32:33], v[126:127], v[154:155], v[46:47] op_sel_hi:[1,0,1]
	v_pk_fma_f32 v[34:35], v[124:125], v[156:157], v[52:53] op_sel_hi:[1,0,1]
	v_pk_fma_f32 v[36:37], v[126:127], v[156:157], v[54:55] op_sel_hi:[1,0,1]
	v_pk_fma_f32 v[38:39], v[124:125], v[158:159], v[48:49] op_sel_hi:[1,0,1]
	v_pk_fma_f32 v[44:45], v[126:127], v[158:159], v[50:51] op_sel_hi:[1,0,1]
	v_pk_fma_f32 v[40:41], v[124:125], v[138:139], v[40:41] op_sel_hi:[1,0,1]
	v_pk_fma_f32 v[20:21], v[126:127], v[138:139], v[20:21] op_sel_hi:[1,0,1]
	v_pk_fma_f32 v[22:23], v[124:125], v[132:133], v[22:23] op_sel_hi:[1,0,1]
	v_pk_fma_f32 v[16:17], v[126:127], v[132:133], v[16:17] op_sel_hi:[1,0,1]
	v_pk_fma_f32 v[18:19], v[124:125], v[144:145], v[18:19] op_sel_hi:[1,0,1]
	v_pk_fma_f32 v[12:13], v[126:127], v[144:145], v[12:13] op_sel_hi:[1,0,1]
	v_pk_fma_f32 v[14:15], v[124:125], v[146:147], v[14:15] op_sel_hi:[1,0,1]
	v_pk_fma_f32 v[8:9], v[126:127], v[146:147], v[8:9] op_sel_hi:[1,0,1]
	v_pk_fma_f32 v[10:11], v[124:125], v[160:161], v[10:11] op_sel_hi:[1,0,1]
	v_pk_fma_f32 v[4:5], v[126:127], v[160:161], v[4:5] op_sel_hi:[1,0,1]
	s_waitcnt vmcnt(3)
	v_pk_fma_f32 v[6:7], v[120:121], v[0:1], v[6:7] op_sel_hi:[1,0,1]
	v_pk_fma_f32 v[24:25], v[122:123], v[0:1], v[24:25] op_sel_hi:[1,0,1]
	s_waitcnt lgkmcnt(7)
	v_pk_fma_f32 v[28:29], v[120:121], v[76:77], v[28:29] op_sel_hi:[1,0,1]
	v_pk_fma_f32 v[32:33], v[122:123], v[76:77], v[32:33] op_sel_hi:[1,0,1]
	s_waitcnt lgkmcnt(6)
	v_pk_fma_f32 v[34:35], v[120:121], v[80:81], v[34:35] op_sel_hi:[1,0,1]
	v_pk_fma_f32 v[36:37], v[122:123], v[80:81], v[36:37] op_sel_hi:[1,0,1]
	s_waitcnt lgkmcnt(5)
	v_pk_fma_f32 v[38:39], v[120:121], v[84:85], v[38:39] op_sel_hi:[1,0,1]
	v_pk_fma_f32 v[44:45], v[122:123], v[84:85], v[44:45] op_sel_hi:[1,0,1]
	s_waitcnt lgkmcnt(4)
	v_pk_fma_f32 v[40:41], v[120:121], v[88:89], v[40:41] op_sel_hi:[1,0,1]
	v_pk_fma_f32 v[20:21], v[122:123], v[88:89], v[20:21] op_sel_hi:[1,0,1]
	s_waitcnt lgkmcnt(3)
	v_pk_fma_f32 v[22:23], v[120:121], v[92:93], v[22:23] op_sel_hi:[1,0,1]
	v_pk_fma_f32 v[16:17], v[122:123], v[92:93], v[16:17] op_sel_hi:[1,0,1]
	s_waitcnt lgkmcnt(2)
	v_pk_fma_f32 v[18:19], v[120:121], v[96:97], v[18:19] op_sel_hi:[1,0,1]
	v_pk_fma_f32 v[12:13], v[122:123], v[96:97], v[12:13] op_sel_hi:[1,0,1]
	s_waitcnt lgkmcnt(1)
	v_pk_fma_f32 v[14:15], v[120:121], v[100:101], v[14:15] op_sel_hi:[1,0,1]
	v_pk_fma_f32 v[8:9], v[122:123], v[100:101], v[8:9] op_sel_hi:[1,0,1]
	s_waitcnt lgkmcnt(0)
	v_pk_fma_f32 v[10:11], v[120:121], v[104:105], v[10:11] op_sel_hi:[1,0,1]
	v_pk_fma_f32 v[4:5], v[122:123], v[104:105], v[4:5] op_sel_hi:[1,0,1]
	s_waitcnt vmcnt(2)
	v_pk_fma_f32 v[6:7], v[116:117], v[0:1], v[6:7] op_sel:[0,1,0]
	v_pk_fma_f32 v[0:1], v[118:119], v[0:1], v[24:25] op_sel:[0,1,0]
	v_pk_fma_f32 v[24:25], v[116:117], v[76:77], v[28:29] op_sel:[0,1,0]
	v_pk_fma_f32 v[28:29], v[118:119], v[76:77], v[32:33] op_sel:[0,1,0]
	v_pk_fma_f32 v[32:33], v[116:117], v[80:81], v[34:35] op_sel:[0,1,0]
	v_pk_fma_f32 v[34:35], v[118:119], v[80:81], v[36:37] op_sel:[0,1,0]
	v_pk_fma_f32 v[36:37], v[116:117], v[84:85], v[38:39] op_sel:[0,1,0]
	v_pk_fma_f32 v[38:39], v[118:119], v[84:85], v[44:45] op_sel:[0,1,0]
	v_pk_fma_f32 v[40:41], v[116:117], v[88:89], v[40:41] op_sel:[0,1,0]
	v_pk_fma_f32 v[20:21], v[118:119], v[88:89], v[20:21] op_sel:[0,1,0]
	v_pk_fma_f32 v[22:23], v[116:117], v[92:93], v[22:23] op_sel:[0,1,0]
	v_pk_fma_f32 v[16:17], v[118:119], v[92:93], v[16:17] op_sel:[0,1,0]
	v_pk_fma_f32 v[18:19], v[116:117], v[96:97], v[18:19] op_sel:[0,1,0]
	v_pk_fma_f32 v[12:13], v[118:119], v[96:97], v[12:13] op_sel:[0,1,0]
	v_pk_fma_f32 v[14:15], v[116:117], v[100:101], v[14:15] op_sel:[0,1,0]
	v_pk_fma_f32 v[8:9], v[118:119], v[100:101], v[8:9] op_sel:[0,1,0]
	v_pk_fma_f32 v[10:11], v[116:117], v[104:105], v[10:11] op_sel:[0,1,0]
	v_pk_fma_f32 v[4:5], v[118:119], v[104:105], v[4:5] op_sel:[0,1,0]
	v_mov_b32_e32 v26, v3
	v_mov_b32_e32 v30, v79
	v_mov_b32_e32 v42, v83
	v_mov_b32_e32 v60, v87
	v_mov_b32_e32 v64, v91
	v_mov_b32_e32 v68, v95
	v_mov_b32_e32 v66, v99
	v_mov_b32_e32 v70, v103
	v_mov_b32_e32 v62, v107
	s_waitcnt vmcnt(1)
	v_pk_fma_f32 v[6:7], v[112:113], v[2:3], v[6:7] op_sel_hi:[1,0,1]
	v_pk_fma_f32 v[0:1], v[114:115], v[2:3], v[0:1] op_sel_hi:[1,0,1]
	v_pk_fma_f32 v[2:3], v[112:113], v[78:79], v[24:25] op_sel_hi:[1,0,1]
	v_pk_fma_f32 v[24:25], v[114:115], v[78:79], v[28:29] op_sel_hi:[1,0,1]
	v_pk_fma_f32 v[28:29], v[112:113], v[82:83], v[32:33] op_sel_hi:[1,0,1]
	v_pk_fma_f32 v[32:33], v[114:115], v[82:83], v[34:35] op_sel_hi:[1,0,1]
	v_pk_fma_f32 v[34:35], v[112:113], v[86:87], v[36:37] op_sel_hi:[1,0,1]
	v_pk_fma_f32 v[36:37], v[114:115], v[86:87], v[38:39] op_sel_hi:[1,0,1]
	v_pk_fma_f32 v[38:39], v[112:113], v[90:91], v[40:41] op_sel_hi:[1,0,1]
	v_pk_fma_f32 v[20:21], v[114:115], v[90:91], v[20:21] op_sel_hi:[1,0,1]
	v_pk_fma_f32 v[22:23], v[112:113], v[94:95], v[22:23] op_sel_hi:[1,0,1]
	v_pk_fma_f32 v[16:17], v[114:115], v[94:95], v[16:17] op_sel_hi:[1,0,1]
	v_pk_fma_f32 v[18:19], v[112:113], v[98:99], v[18:19] op_sel_hi:[1,0,1]
	v_pk_fma_f32 v[12:13], v[114:115], v[98:99], v[12:13] op_sel_hi:[1,0,1]
	v_pk_fma_f32 v[14:15], v[112:113], v[102:103], v[14:15] op_sel_hi:[1,0,1]
	v_pk_fma_f32 v[8:9], v[114:115], v[102:103], v[8:9] op_sel_hi:[1,0,1]
	v_pk_fma_f32 v[10:11], v[112:113], v[106:107], v[10:11] op_sel_hi:[1,0,1]
	v_pk_fma_f32 v[4:5], v[114:115], v[106:107], v[4:5] op_sel_hi:[1,0,1]
	s_waitcnt vmcnt(0)
	v_pk_fma_f32 v[44:45], v[108:109], v[26:27], v[6:7] op_sel_hi:[1,0,1]
	v_pk_fma_f32 v[46:47], v[110:111], v[26:27], v[0:1] op_sel_hi:[1,0,1]
	v_pk_fma_f32 v[56:57], v[108:109], v[30:31], v[2:3] op_sel_hi:[1,0,1]
	v_pk_fma_f32 v[58:59], v[110:111], v[30:31], v[24:25] op_sel_hi:[1,0,1]
	v_pk_fma_f32 v[52:53], v[108:109], v[42:43], v[28:29] op_sel_hi:[1,0,1]
	v_pk_fma_f32 v[54:55], v[110:111], v[42:43], v[32:33] op_sel_hi:[1,0,1]
	v_pk_fma_f32 v[48:49], v[108:109], v[60:61], v[34:35] op_sel_hi:[1,0,1]
	v_pk_fma_f32 v[50:51], v[110:111], v[60:61], v[36:37] op_sel_hi:[1,0,1]
	v_pk_fma_f32 v[40:41], v[108:109], v[64:65], v[38:39] op_sel_hi:[1,0,1]
	v_pk_fma_f32 v[42:43], v[110:111], v[64:65], v[20:21] op_sel_hi:[1,0,1]
	v_pk_fma_f32 v[36:37], v[108:109], v[68:69], v[22:23] op_sel_hi:[1,0,1]
	v_pk_fma_f32 v[38:39], v[110:111], v[68:69], v[16:17] op_sel_hi:[1,0,1]
	v_pk_fma_f32 v[32:33], v[108:109], v[66:67], v[18:19] op_sel_hi:[1,0,1]
	v_pk_fma_f32 v[34:35], v[110:111], v[66:67], v[12:13] op_sel_hi:[1,0,1]
	v_pk_fma_f32 v[28:29], v[108:109], v[70:71], v[14:15] op_sel_hi:[1,0,1]
	v_pk_fma_f32 v[30:31], v[110:111], v[70:71], v[8:9] op_sel_hi:[1,0,1]
	v_pk_fma_f32 v[24:25], v[108:109], v[62:63], v[10:11] op_sel_hi:[1,0,1]
	v_pk_fma_f32 v[26:27], v[110:111], v[62:63], v[4:5] op_sel_hi:[1,0,1]
	s_cbranch_scc0 .LBB0_84
	v_and_b32_e32 v0, 60, v135
	s_movk_i32 s0, 0x900
	v_lshlrev_b32_e32 v0, 2, v0
	v_mul_lo_u32 v1, v141, s0
	s_movk_i32 s0, 0x240
	v_add3_u32 v0, 0, v0, v1
	v_cmp_gt_i32_e32 vcc, s0, v134
	ds_write_b128 v0, v[44:47] offset:36864
	ds_write_b128 v0, v[56:59] offset:37120
	ds_write_b128 v0, v[52:55] offset:37376
	ds_write_b128 v0, v[48:51] offset:37632
	ds_write_b128 v0, v[40:43] offset:37888
	ds_write_b128 v0, v[36:39] offset:38144
	ds_write_b128 v0, v[32:35] offset:38400
	ds_write_b128 v0, v[28:31] offset:38656
	ds_write_b128 v0, v[24:27] offset:38912
	s_waitcnt lgkmcnt(0)
	s_barrier
	s_and_saveexec_b64 s[0:1], vcc
	s_cbranch_execz .LBB0_19
	s_add_u32 s8, s47, s38
	s_addc_u32 s9, s48, s39
	s_mul_i32 s7, s36, 0x9000
	s_mul_hi_i32 s6, s36, 0x9000
	s_add_u32 s7, s82, s7
	s_addc_u32 s6, s83, s6
	s_add_u32 s10, s7, s38
	s_addc_u32 s11, s6, s39
	v_and_b32_e32 v132, 0xfc, v140
	s_mul_hi_i32 s7, s36, 9
	s_mul_i32 s6, s36, 9
	v_add_u32_e32 v4, 0, v132
	v_lshl_add_u64 v[0:1], s[10:11], 0, v[132:133]
	v_lshl_add_u64 v[2:3], s[8:9], 0, v[132:133]
	s_mov_b64 s[8:9], 0

.LBB0_147:
	v_writelane_b32 v251, s72, 38
	s_nop 1
	v_writelane_b32 v251, s73, 39
	v_writelane_b32 v251, s74, 40
	v_writelane_b32 v251, s75, 41
	v_writelane_b32 v251, s76, 42
	v_writelane_b32 v251, s77, 43
	v_writelane_b32 v251, s78, 44
	v_writelane_b32 v251, s79, 45
	v_writelane_b32 v251, s80, 46
	v_writelane_b32 v251, s81, 47
	v_writelane_b32 v251, s82, 48
	v_writelane_b32 v251, s83, 49
	v_writelane_b32 v251, s84, 50
	v_writelane_b32 v251, s85, 51
	v_writelane_b32 v251, s86, 52
	v_writelane_b32 v251, s87, 53
	s_or_b64 exec, exec, s[0:1]
	v_readlane_b32 s2, v251, 36
	s_cmpk_lt_i32 s2, 0x19e0
	s_cselect_b64 s[4:5], -1, 0
	s_add_u32 s62, s92, 0x1f4e0000
	s_addc_u32 s63, s93, 0
	s_add_u32 s33, s92, 0x1f1e0000
	v_readlane_b32 s3, v251, 37
	v_writelane_b32 v251, s4, 54
	s_addc_u32 s35, s93, 0
	s_mul_i32 s0, s95, s94
	v_writelane_b32 v251, s5, 55
	s_add_u32 s4, s92, 0x1e420000
	s_addc_u32 s5, s93, 0
	s_add_u32 s34, s92, 0x1d920000
	v_writelane_b32 v251, s4, 56
	s_addc_u32 s27, s93, 0
	s_add_u32 s1, s92, 0x1c320000
	v_writelane_b32 v251, s5, 57
	v_writelane_b32 v251, s1, 58
	s_addc_u32 s1, s93, 0
	v_writelane_b32 v251, s1, 59
	s_lshl_b32 s1, s2, 2
	s_lshl_b32 s8, s94, 2
	v_writelane_b32 v251, s1, 60
	s_add_u32 s1, s92, 0x250e0000
	v_writelane_b32 v251, s1, 61
	s_addc_u32 s1, s93, 0
	s_add_u32 s82, s92, 0x4800000
	s_addc_u32 s83, s93, 0
	s_mul_i32 s24, s0, s61
	s_add_u32 s0, s92, 0x25467800
	v_writelane_b32 v251, s1, 62
	s_addc_u32 s1, s93, 0
	v_writelane_b32 v251, s0, 63
	s_mov_b64 s[6:7], src_shared_base
	s_mov_b64 s[96:97], 0x1400
	v_writelane_b32 v250, s1, 0
	s_add_u32 s0, s92, 0x25467a00
	s_addc_u32 s1, s93, 0
	v_writelane_b32 v250, s0, 1
	v_mov_b32_e32 v97, 0
	v_mbcnt_lo_u32_b32 v195, -1, 0
	v_writelane_b32 v250, s1, 2
	s_add_u32 s0, s92, 0x25467b00
	s_addc_u32 s1, s93, 0
	v_writelane_b32 v250, s0, 3
	v_mov_b32_e32 v163, 0x358637bd
	v_mov_b32_e32 v190, 1
	v_writelane_b32 v250, s1, 4
	s_add_u32 s0, s92, 0x25467c00
	s_addc_u32 s1, s93, 0
	v_writelane_b32 v250, s0, 5
	v_mov_b32_e32 v191, 0x3ecc95a3
	v_mov_b32_e32 v192, 0x3ab69700
	v_writelane_b32 v250, s1, 6
	s_add_u32 s0, s92, 0x25467d00
	s_addc_u32 s1, s93, 0
	v_writelane_b32 v250, s0, 7
	v_mov_b32_e32 v193, 0x260
	v_mov_b32_e32 v194, 0xb00000
	v_writelane_b32 v250, s1, 8
	s_add_u32 s0, s92, 0x25467e00
	s_addc_u32 s1, s93, 0
	v_writelane_b32 v250, s0, 9
	v_mbcnt_hi_u32_b32 v196, -1, v195
	v_mov_b32_e32 v197, 0x42800000
	v_writelane_b32 v250, s1, 10
	s_add_u32 s0, s92, 0x25467f00
	s_addc_u32 s1, s93, 0
	v_writelane_b32 v250, s0, 11
	v_not_b32_e32 v198, 63
	v_mov_b32_e32 v168, 0x3f317218
	v_writelane_b32 v250, s1, 12
	s_add_u32 s0, s92, 0x25468000
	s_addc_u32 s1, s93, 0
	v_writelane_b32 v250, s0, 13
	v_mov_b32_e32 v199, 0x7f800000
	v_mov_b32_e32 v200, 0x7fc00000
	v_writelane_b32 v250, s1, 14
	s_add_u32 s0, s92, 0x25468100
	s_addc_u32 s1, s93, 0
	v_writelane_b32 v250, s0, 15
	v_mov_b32_e32 v201, 0xff800000
	v_mov_b32_e32 v202, 0x7f000000
	v_writelane_b32 v250, s1, 16
	s_add_u32 s0, s92, 0x25468200
	s_addc_u32 s1, s93, 0
	v_writelane_b32 v250, s0, 17
	v_bfrev_b32_e32 v203, 0.5
	v_mov_b32_e32 v204, 0xf149f2ca
	v_writelane_b32 v250, s1, 18
	s_add_u32 s0, s92, 0x25468300
	s_addc_u32 s1, s93, 0
	v_writelane_b32 v250, s0, 19
	v_mov_b32_e32 v240, v97
	v_mov_b32_e32 v241, v97
	v_writelane_b32 v250, s1, 20
	s_add_u32 s0, s92, 0x25468400
	s_addc_u32 s1, s93, 0
	v_writelane_b32 v250, s0, 21
	v_mov_b32_e32 v205, 0xff61b1e6
	s_mov_b32 s86, 0x800000
	v_writelane_b32 v250, s1, 22
	s_add_u32 s0, s92, 0x25468500
	s_addc_u32 s1, s93, 0
	v_writelane_b32 v250, s0, 23
	s_mov_b32 s28, 0x4800000
	s_movk_i32 s29, 0x47ff
	v_writelane_b32 v250, s1, 24
	s_add_u32 s0, s92, 0x25468600
	s_addc_u32 s1, s93, 0
	v_writelane_b32 v250, s0, 25
	s_movk_i32 s84, 0x48
	s_mov_b32 s81, 0x1fffffc0
	v_writelane_b32 v250, s1, 26
	s_add_u32 s0, s92, 0x25468700
	s_addc_u32 s1, s93, 0
	v_writelane_b32 v250, s0, 27
	s_movk_i32 s18, 0x1600
	s_mov_b32 s19, 0x2c000
	v_writelane_b32 v250, s1, 28
	s_add_u32 s0, s92, 0x25468800
	s_addc_u32 s1, s93, 0
	v_writelane_b32 v250, s0, 29
	s_mov_b32 s20, 0x58000
	s_mov_b32 s21, 0x84000
	v_writelane_b32 v250, s1, 30
	s_add_u32 s0, s92, 0x25468900
	s_addc_u32 s1, s93, 0
	v_writelane_b32 v250, s0, 31
	s_cmp_eq_u32 s60, 15
	s_mov_b32 s22, 0x2d000
	v_writelane_b32 v250, s1, 32
	s_cselect_b64 s[0:1], -1, 0
	v_writelane_b32 v250, s0, 33
	s_cmp_eq_u32 s60, 14
	s_mov_b32 s23, 0x59000
	v_writelane_b32 v250, s1, 34
	s_cselect_b64 s[0:1], -1, 0
	v_writelane_b32 v250, s0, 35
	s_cmp_eq_u32 s60, 13
	s_mov_b32 s25, 0x85000
	v_writelane_b32 v250, s1, 36
	s_cselect_b64 s[0:1], -1, 0
	v_writelane_b32 v250, s0, 37
	s_cmp_eq_u32 s60, 12
	s_movk_i32 s74, 0x3600
	v_writelane_b32 v250, s1, 38
	s_cselect_b64 s[0:1], -1, 0
	v_writelane_b32 v250, s0, 39
	s_cmp_eq_u32 s60, 11
	s_mov_b32 s79, 0xffff0000
	v_writelane_b32 v250, s1, 40
	s_cselect_b64 s[0:1], -1, 0
	v_writelane_b32 v250, s0, 41
	s_cmp_eq_u32 s60, 10
	s_movk_i32 s87, 0x110
	v_writelane_b32 v250, s1, 42
	s_cselect_b64 s[0:1], -1, 0
	v_writelane_b32 v250, s0, 43
	s_cmp_eq_u32 s60, 9
	s_movk_i32 s80, 0x2ff
	v_writelane_b32 v250, s1, 44
	s_cselect_b64 s[0:1], -1, 0
	v_writelane_b32 v250, s0, 45
	s_cmp_eq_u32 s60, 8
	s_mov_b32 s85, 0x6c000
	v_writelane_b32 v250, s1, 46
	s_cselect_b64 s[0:1], -1, 0
	v_writelane_b32 v250, s0, 47
	s_cmp_eq_u32 s60, 7
	s_movk_i32 s58, 0x101
	v_writelane_b32 v250, s1, 48
	v_readlane_b32 s0, v251, 2
	v_readlane_b32 s1, v251, 3
	s_mov_b32 s59, 0xff61b1e6
	s_movk_i32 s77, 0x6ff
	v_lshl_add_u64 v[0:1], v[0:1], 2, s[0:1]
	s_mov_b64 s[0:1], 0x2400
	v_lshl_add_u64 v[164:165], v[0:1], 0, s[0:1]
	s_cselect_b64 s[0:1], -1, 0
	v_writelane_b32 v250, s0, 49
	s_cmp_eq_u32 s60, 6
	v_lshl_add_u64 v[166:167], v[0:1], 0, s[96:97]
	v_writelane_b32 v250, s1, 50
	s_cselect_b64 s[0:1], -1, 0
	v_writelane_b32 v250, s0, 51
	s_cmp_eq_u32 s60, 5
	s_mov_b64 s[36:37], 0x800
	v_writelane_b32 v250, s1, 52
	s_cselect_b64 s[0:1], -1, 0
	v_writelane_b32 v250, s0, 53
	s_cmp_eq_u32 s60, 4
	v_writelane_b32 v250, s1, 54
	s_cselect_b64 s[0:1], -1, 0
	v_writelane_b32 v250, s0, 55
	s_cmp_eq_u32 s60, 3
	s_barrier
	v_writelane_b32 v250, s1, 56
	s_cselect_b64 s[0:1], -1, 0
	v_writelane_b32 v250, s0, 57
	s_cmp_eq_u32 s60, 2
	s_nop 0
	v_writelane_b32 v250, s1, 58
	s_cselect_b64 s[0:1], -1, 0
	v_writelane_b32 v250, s0, 59
	s_cmp_eq_u32 s60, 1
	v_writelane_b32 v250, s1, 60
	s_cselect_b64 s[0:1], -1, 0
	v_writelane_b32 v250, s0, 61
	s_cmp_eq_u32 s60, 0
	v_writelane_b32 v250, s1, 62
	s_cselect_b64 s[0:1], -1, 0
	v_writelane_b32 v250, s0, 63
	v_writelane_b32 v249, s1, 0
	s_add_u32 s0, s92, 0x2546aa00
	s_addc_u32 s1, s93, 0
	v_writelane_b32 v249, s0, 1
	v_writelane_b32 v249, s1, 2
	s_add_u32 s0, s92, 0x2546ab00
	s_addc_u32 s1, s93, 0
	s_add_u32 s56, s92, 0x6c00000
	s_addc_u32 s57, s93, 0
	v_writelane_b32 v249, s0, 3
	s_cmpk_lt_i32 s2, 0x18c0
	v_writelane_b32 v249, s1, 4
	s_cselect_b64 s[0:1], -1, 0
	v_writelane_b32 v249, s0, 5
	v_writelane_b32 v249, s1, 6
	s_add_u32 s0, s92, 0xcf00000
	s_addc_u32 s1, s93, 0
	v_writelane_b32 v249, s0, 7
	s_cmpk_lt_i32 s2, 0xfc0
	v_writelane_b32 v249, s1, 8
	s_cselect_b64 s[0:1], -1, 0
	v_writelane_b32 v249, s0, 9
	v_writelane_b32 v249, s1, 10
	s_add_u32 s0, s92, 0xb400000
	s_addc_u32 s1, s93, 0
	v_writelane_b32 v249, s0, 11
	v_writelane_b32 v249, s1, 12
	s_add_u32 s0, s92, 0xcf01800
	s_addc_u32 s1, s93, 0
	v_writelane_b32 v249, s0, 13
	v_writelane_b32 v249, s1, 14
	s_add_u32 s0, s92, 0x25347600
	s_addc_u32 s1, s93, 0
	v_writelane_b32 v249, s0, 15
	v_writelane_b32 v249, s1, 16
	s_add_u32 s0, s92, 0x1c200000
	s_addc_u32 s1, s93, 0
	s_add_u32 s95, s92, 0x252b4000
	s_addc_u32 s76, s93, 0
	v_writelane_b32 v249, s0, 17
	s_cmp_lg_u32 0, -1
	v_writelane_b32 v249, s1, 18
	s_cselect_b64 s[0:1], -1, 0
	v_writelane_b32 v249, s0, 19
	v_writelane_b32 v249, s1, 20
	s_add_u32 s0, s92, 0x25224000
	s_addc_u32 s1, s93, 0
	v_writelane_b32 v249, s0, 21
	v_writelane_b32 v249, s1, 22
	s_add_u32 s0, s92, 0xc600000
	v_writelane_b32 v249, s0, 23
	s_addc_u32 s0, s93, 0
	v_writelane_b32 v249, s0, 24
	s_add_u32 s0, s92, 0x21ae0000
	v_writelane_b32 v249, s0, 25
	s_addc_u32 s0, s93, 0
	v_writelane_b32 v249, s0, 26
	s_add_u32 s0, s92, 0x22ce0000
	s_addc_u32 s1, s93, 0
	v_writelane_b32 v249, s0, 27
	v_writelane_b32 v249, s1, 28
	s_add_u32 s0, s92, 0x252b6400
	s_addc_u32 s1, s93, 0
	s_add_u32 s78, s92, 0x25346400
	s_addc_u32 s72, s93, 0
	s_add_u32 s64, s92, 0x1f6e0000
	v_writelane_b32 v249, s0, 29
	s_addc_u32 s65, s93, 0
	v_writelane_b32 v249, s1, 30
	s_add_u32 s0, s92, 0xcf00400
	s_addc_u32 s1, s93, 0
	s_add_u32 s66, s92, 0x208e0000
	v_writelane_b32 v249, s0, 31
	s_addc_u32 s67, s93, 0
	v_writelane_b32 v249, s1, 32
	s_add_u32 s0, s92, 0x1ce20000
	v_writelane_b32 v249, s0, 33
	s_addc_u32 s0, s93, 0
	v_writelane_b32 v249, s0, 34
	s_add_u32 s0, s92, 0x1dea0000
	v_writelane_b32 v249, s0, 35
	s_addc_u32 s0, s93, 0
	s_abs_i32 s3, s94
	v_cvt_f32_u32_e32 v2, s3
	v_writelane_b32 v249, s0, 36
	s_sub_i32 s0, 0, s3
	v_rcp_iflag_f32_e32 v2, v2
	s_nop 0
	v_mul_f32_e32 v2, 0x4f7ffffe, v2
	v_cvt_u32_f32_e32 v2, v2
	s_nop 0
	v_readfirstlane_b32 s1, v2
	s_mul_i32 s0, s0, s1
	s_mul_hi_u32 s0, s1, s0
	s_add_i32 s0, s1, s0
	v_writelane_b32 v249, s0, 37
	s_mul_hi_u32 s0, s0, 0x480
	s_mul_i32 s0, s0, s3
	s_sub_i32 s0, 0x480, s0
	s_sub_i32 s1, s0, s3
	s_cmp_ge_u32 s0, s3
	s_cselect_b32 s0, s1, s0
	s_sub_i32 s1, s0, s3
	s_cmp_ge_u32 s0, s3
	s_cselect_b32 s0, s1, s0
	v_writelane_b32 v249, s3, 38
	s_sub_i32 s3, 0x480, s0
	s_cmp_lt_i32 s2, s3
	s_cselect_b64 s[4:5], -1, 0
	v_writelane_b32 v249, s4, 39
	v_writelane_b32 v248, s3, 0
	v_writelane_b32 v249, s5, 40
	s_lshl_b32 s4, s0, 1
	s_cmp_lt_i32 s2, s4
	s_cselect_b64 s[0:1], -1, 0
	v_writelane_b32 v249, s0, 41
	s_ashr_i32 s9, s8, 31
	s_lshl_b64 s[30:31], s[8:9], 11
	v_writelane_b32 v249, s1, 42
	s_lshl_b32 s0, s2, 5
	s_add_i32 s0, s0, 0xfffe5000
	v_writelane_b32 v249, s0, 43
	s_lshl_b32 s0, s94, 5
	s_lshl_b64 s[14:15], s[8:9], 12
	v_writelane_b32 v249, s0, 44
	s_add_u32 s0, s92, 0x25349600
	v_writelane_b32 v249, s0, 45
	s_addc_u32 s0, s93, 0
	v_writelane_b32 v249, s0, 46
	s_add_u32 s0, s92, 0x25346600
	v_writelane_b32 v249, s0, 47
	s_addc_u32 s0, s93, 0
	v_writelane_b32 v249, s0, 48
	s_add_i32 s0, 0, 0x13ff0
	v_writelane_b32 v249, s0, 49
	s_add_i32 s0, 0, 0x13ff4
	v_writelane_b32 v249, s0, 50
	s_add_i32 s0, 0, 0x11800
	v_writelane_b32 v249, s0, 51
	s_add_i32 s0, 0, 0x8c00
	v_writelane_b32 v249, s0, 52
	s_add_i32 s0, 0, 0x8800
	v_writelane_b32 v249, s0, 53
	s_add_i32 s0, 0, 0x11c00
	v_writelane_b32 v249, s0, 54
	s_add_i32 s0, 0, 0x11a00
	v_writelane_b32 v248, s4, 1
	v_writelane_b32 v249, s0, 55
	s_mov_b32 s1, s7
	v_writelane_b32 v248, s30, 2
	v_writelane_b32 v249, s0, 56
	s_mov_b32 s2, 0
	v_writelane_b32 v248, s31, 3
	v_writelane_b32 v249, s1, 57
	v_writelane_b32 v248, s14, 4
	v_writelane_b32 v249, s62, 58
	s_mov_b32 s0, s8
	v_writelane_b32 v248, s15, 5
	v_writelane_b32 v249, s63, 59
	v_writelane_b32 v248, s34, 6
	v_writelane_b32 v249, s0, 60
	v_writelane_b32 v248, s24, 7
	v_writelane_b32 v248, s82, 8
	v_writelane_b32 v249, s1, 61
	s_mov_b32 s5, 0
	v_writelane_b32 v249, s56, 62
	v_writelane_b32 v248, s83, 9
	v_writelane_b32 v248, s27, 10
	v_writelane_b32 v249, s57, 63
	s_branch .LBB0_151

.LBB0_209:
	v_readlane_b32 s3, v248, 11
	s_mul_i32 s1, s3, 0x51000
	v_readlane_b32 s2, v251, 61
	v_mov_b32_e32 v1, v162
	v_mov_b32_e32 v0, v162
	s_mul_hi_u32 s0, s3, 0x51000
	s_add_u32 s16, s2, s1
	v_readlane_b32 s1, v251, 62
	s_addc_u32 s17, s1, s0
	v_ashrrev_i32_e32 v0, 6, v0
	v_readlane_b32 s0, v251, 60
	v_readlane_b32 s100, v251, 36
	s_cmpk_lg_u32 s94, 0x200
	s_cbranch_scc1 .Lnrm_orig0
	s_lshr_b32 s101, s100, 3
	s_lshl_b32 s101, s101, 2
	v_add_u32_e32 v0, s101, v0
	s_and_b32 s100, s100, 7
	s_lshl_b32 s100, s100, 7
	v_lshrrev_b32_e32 v255, 7, v0
	v_and_b32_e32 v0, 0x7f, v0
	v_lshl_add_u32 v0, v255, 10, v0
	v_add_u32_e32 v0, s100, v0
	s_branch .Lnrm_done0

.LBB0_211:
	v_lshl_add_u64 v[36:37], s[92:93], 0, v[6:7]
	global_load_dwordx4 v[16:19], v[2:3], off offset:16
	global_load_dwordx4 v[20:23], v[2:3], off
	global_load_dwordx4 v[24:27], v[36:37], off
	global_load_dwordx4 v[28:31], v[36:37], off offset:16
	global_load_dwordx4 v[32:35], v[36:37], off offset:2048
	s_nop 0
	global_load_dwordx4 v[36:39], v[36:37], off offset:2064
	v_min_i32_e32 v1, 0x4000, v0
	v_lshl_add_u64 v[40:41], s[92:93], 0, v[4:5]
	v_ashrrev_i32_e32 v1, 11, v1
	v_add_co_u32_e32 v56, vcc, s28, v40
	v_mul_i32_i24_e32 v40, 0x9000, v1
	s_nop 0
	v_addc_co_u32_e32 v57, vcc, 0, v41, vcc
	v_mul_hi_i32_i24_e32 v41, 0x9000, v1
	v_lshl_add_u64 v[40:41], s[16:17], 0, v[40:41]
	v_lshl_add_u64 v[48:49], v[40:41], 0, s[6:7]
	v_mov_b32_e32 v9, v97
	v_lshl_add_u64 v[58:59], v[40:41], 0, v[96:97]
	v_lshl_add_u64 v[52:53], v[48:49], 0, v[96:97]
	global_load_dwordx4 v[40:43], v[58:59], off offset:16
	global_load_dwordx4 v[44:47], v[58:59], off
	v_lshl_add_u64 v[60:61], v[48:49], 0, v[8:9]
	global_load_dwordx4 v[48:51], v[52:53], off offset:16
	global_load_dwordx4 v[52:55], v[52:53], off
	global_load_dwordx4 v[86:89], v[2:3], off offset:2048
	global_load_dwordx4 v[90:93], v[60:61], off
	global_load_dwordx4 v[98:101], v[2:3], off offset:2064
	global_load_dwordx4 v[106:109], v[60:61], off offset:16
	global_load_dwordx4 v[110:113], v[58:59], off offset:2048
	global_load_dwordx4 v[114:117], v[58:59], off offset:2064
	v_add_u32_e32 v0, s8, v0
	v_lshl_add_u64 v[4:5], v[4:5], 0, s[30:31]
	v_lshl_add_u64 v[6:7], v[6:7], 0, s[14:15]
	s_waitcnt vmcnt(13)
	v_mov_b32_e32 v68, v25
	s_waitcnt vmcnt(12)
	v_mov_b32_e32 v69, v29
	v_mov_b32_e32 v66, v24
	v_mov_b32_e32 v67, v28
	s_waitcnt vmcnt(11)
	v_mov_b32_e32 v76, v33
	s_waitcnt vmcnt(10)
	v_mov_b32_e32 v77, v37
	v_pk_mul_f32 v[68:69], v[68:69], v[68:69]
	v_mov_b32_e32 v62, v26
	v_mov_b32_e32 v63, v30
	v_mov_b32_e32 v74, v32
	v_mov_b32_e32 v75, v36
	v_pk_mul_f32 v[76:77], v[76:77], v[76:77]
	v_pk_fma_f32 v[66:67], v[66:67], v[66:67], v[68:69]
	v_mov_b32_e32 v64, v27
	v_mov_b32_e32 v65, v31
	v_mov_b32_e32 v70, v34
	v_mov_b32_e32 v71, v38
	v_pk_fma_f32 v[68:69], v[74:75], v[74:75], v[76:77]
	v_pk_fma_f32 v[62:63], v[62:63], v[62:63], v[66:67]
	v_mov_b32_e32 v72, v35
	v_mov_b32_e32 v73, v39
	v_pk_fma_f32 v[66:67], v[70:71], v[70:71], v[68:69]
	v_pk_fma_f32 v[62:63], v[64:65], v[64:65], v[62:63]
	v_pk_fma_f32 v[64:65], v[72:73], v[72:73], v[66:67]
	v_add_f32_e32 v1, v62, v63
	v_add_f32_e32 v1, v1, v64
	v_add_f32_e32 v1, v1, v65
	v_mov_b32_e32 v9, v1
	v_mov_b32_e32 v255, v1
	s_nop 1
	v_permlane32_swap_b32_e32 v9, v255
	s_waitcnt vmcnt(7)
	v_pk_add_f32 v[48:49], v[48:49], 1.0 op_sel_hi:[1,0]
	s_waitcnt vmcnt(6)
	v_pk_add_f32 v[54:55], v[54:55], 1.0 op_sel_hi:[1,0]
	v_pk_add_f32 v[52:53], v[52:53], 1.0 op_sel_hi:[1,0]
	v_pk_add_f32 v[50:51], v[50:51], 1.0 op_sel_hi:[1,0]
	s_waitcnt lgkmcnt(0)
	v_add_f32_e32 v1, v9, v255
	v_mov_b32_e32 v9, v1
	v_mov_b32_e32 v255, v1
	s_nop 1
	v_permlane16_swap_b32_e32 v9, v255
	s_nop 1
	v_mov_b32_dpp v9, v255 quad_perm:[0,1,2,3] row_mask:0x5 bank_mask:0xf
	s_nop 0
	v_add_f32_e32 v1, v1, v9
	s_nop 1
	v_mov_b32_dpp v9, v1 row_ror:8 row_mask:0xf bank_mask:0xf
	s_nop 0
	v_add_f32_e32 v1, v1, v9
	s_nop 1
	v_mov_b32_dpp v9, v1 row_shl:4 row_mask:0xf bank_mask:0x5
	v_mov_b32_dpp v9, v1 row_shr:4 row_mask:0xf bank_mask:0xa
	s_nop 0
	v_add_f32_e32 v1, v1, v9
	s_nop 1
	v_mov_b32_dpp v9, v1 quad_perm:[2,3,0,1] row_mask:0xf bank_mask:0xf
	v_add_f32_e32 v1, v1, v9
	s_nop 1
	v_add_f32_dpp v1, v1, v1 quad_perm:[1,0,3,2] row_mask:0xf bank_mask:0xf
	v_fmamk_f32 v1, v1, 0x3a800000, v163
	v_mul_f32_e32 v9, 0x4b800000, v1
	v_cmp_gt_f32_e32 vcc, s86, v1
	s_nop 1
	v_cndmask_b32_e32 v1, v1, v9, vcc
	v_rsq_f32_e32 v1, v1
	s_nop 0
	v_mul_f32_e32 v9, 0x45800000, v1
	v_cndmask_b32_e32 v62, v1, v9, vcc
	v_pk_mul_f32 v[24:25], v[24:25], v[62:63] op_sel_hi:[1,0]
	v_pk_mul_f32 v[26:27], v[26:27], v[62:63] op_sel_hi:[1,0]
	v_pk_mul_f32 v[28:29], v[28:29], v[62:63] op_sel_hi:[1,0]
	v_pk_mul_f32 v[30:31], v[30:31], v[62:63] op_sel_hi:[1,0]
	v_pk_mul_f32 v[20:21], v[20:21], v[24:25]
	v_pk_mul_f32 v[22:23], v[22:23], v[26:27]
	v_pk_mul_f32 v[16:17], v[28:29], v[16:17]
	v_pk_mul_f32 v[18:19], v[30:31], v[18:19]
	v_pk_fma_f32 v[20:21], v[52:53], v[20:21], v[44:45]
	v_pk_fma_f32 v[22:23], v[54:55], v[22:23], v[46:47]
	v_pk_fma_f32 v[24:25], v[16:17], v[48:49], v[40:41]
	v_pk_fma_f32 v[26:27], v[18:19], v[50:51], v[42:43]
	v_cvt_pk_bf16_f32 v16, v20, v21
	v_cvt_pk_bf16_f32 v17, v22, v23
	v_cvt_pk_bf16_f32 v18, v24, v25
	v_cvt_pk_bf16_f32 v19, v26, v27
	global_store_dwordx4 v[56:57], v[16:19], off
	v_pk_mul_f32 v[32:33], v[32:33], v[62:63] op_sel_hi:[1,0]
	v_pk_mul_f32 v[34:35], v[34:35], v[62:63] op_sel_hi:[1,0]
	v_pk_mul_f32 v[36:37], v[36:37], v[62:63] op_sel_hi:[1,0]
	v_pk_mul_f32 v[38:39], v[38:39], v[62:63] op_sel_hi:[1,0]
	v_cmp_lt_i32_e32 vcc, s29, v0
	s_or_b64 s[2:3], vcc, s[2:3]
	s_waitcnt vmcnt(6)
	v_pk_mul_f32 v[16:17], v[32:33], v[86:87]
	s_waitcnt vmcnt(5)
	v_pk_add_f32 v[20:21], v[90:91], 1.0 op_sel_hi:[1,0]
	v_pk_mul_f32 v[18:19], v[34:35], v[88:89]
	v_pk_add_f32 v[22:23], v[92:93], 1.0 op_sel_hi:[1,0]
	s_waitcnt vmcnt(4)
	v_pk_mul_f32 v[24:25], v[36:37], v[98:99]
	s_waitcnt vmcnt(3)
	v_pk_add_f32 v[28:29], v[106:107], 1.0 op_sel_hi:[1,0]
	v_pk_mul_f32 v[26:27], v[38:39], v[100:101]
	v_pk_add_f32 v[30:31], v[108:109], 1.0 op_sel_hi:[1,0]
	s_waitcnt vmcnt(2)
	v_pk_fma_f32 v[16:17], v[16:17], v[20:21], v[110:111]
	v_pk_fma_f32 v[18:19], v[18:19], v[22:23], v[112:113]
	s_waitcnt vmcnt(1)
	v_pk_fma_f32 v[20:21], v[24:25], v[28:29], v[114:115]
	v_pk_fma_f32 v[22:23], v[26:27], v[30:31], v[116:117]
	v_cvt_pk_bf16_f32 v16, v16, v17
	v_cvt_pk_bf16_f32 v17, v18, v19
	v_cvt_pk_bf16_f32 v18, v20, v21
	v_cvt_pk_bf16_f32 v19, v22, v23
	global_store_dwordx4 v[56:57], v[16:19], off offset:1024
	s_andn2_b64 exec, exec, s[2:3]
	s_cbranch_execnz .LBB0_211

.LBB0_263:
	s_nop 2
	v_mul_f32_e32 v133, 0xbfb8aa3b, v32
	v_exp_f32_e32 v133, v133
	v_mbcnt_hi_u32_b32 v96, -1, v195
	v_and_b32_e32 v99, 64, v96
	v_xor_b32_e32 v98, 32, v96
	v_add_f32_e32 v133, 1.0, v133
	v_rcp_f32_e32 v138, v133
	v_mul_f32_e32 v133, 0xbfb8aa3b, v33
	v_exp_f32_e32 v133, v133
	v_add_u32_e32 v99, 64, v99
	v_cmp_lt_i32_e32 vcc, v98, v99
	s_sext_i32_i16 s2, s2
	v_add_f32_e32 v133, 1.0, v133
	v_rcp_f32_e32 v139, v133
	v_cndmask_b32_e32 v96, v96, v98, vcc
	v_lshlrev_b32_e32 v96, 2, v96
	v_lshl_or_b32 v134, s2, 6, v174
	v_pk_mul_f32 v[32:33], v[32:33], v[138:139]
	v_lshl_add_u32 v132, s6, 7, v169
	v_pk_mul_f32 v[32:33], v[48:49], v[32:33]
	v_mul_f32_e32 v48, 0xbfb8aa3b, v34
	v_mul_f32_e32 v49, 0xbfb8aa3b, v35
	v_exp_f32_e32 v48, v48
	v_exp_f32_e32 v49, v49
	v_mov_b64_e32 v[98:99], s[56:57]
	v_ashrrev_i32_e32 v135, 31, v134
	v_add_f32_e32 v48, 1.0, v48
	v_add_f32_e32 v49, 1.0, v49
	v_rcp_f32_e32 v48, v48
	v_rcp_f32_e32 v49, v49
	v_mad_i64_i32 v[136:137], s[6:7], v132, s18, v[98:99]
	s_waitcnt lgkmcnt(0)
	v_pk_mul_f32 v[34:35], v[34:35], v[48:49]
	v_cvt_pk_bf16_f32 v48, v32, v33
	v_pk_mul_f32 v[34:35], v[50:51], v[34:35]
	v_mul_f32_e32 v32, 0xbfb8aa3b, v36
	v_cvt_pk_bf16_f32 v49, v34, v35
	v_mul_f32_e32 v33, 0xbfb8aa3b, v37
	v_mul_f32_e32 v34, 0xbfb8aa3b, v38
	v_mul_f32_e32 v35, 0xbfb8aa3b, v39
	v_exp_f32_e32 v32, v32
	v_exp_f32_e32 v33, v33
	v_exp_f32_e32 v34, v34
	v_exp_f32_e32 v35, v35
	v_add_f32_e32 v32, 1.0, v32
	v_add_f32_e32 v33, 1.0, v33
	v_add_f32_e32 v34, 1.0, v34
	v_add_f32_e32 v35, 1.0, v35
	v_rcp_f32_e32 v32, v32
	v_rcp_f32_e32 v33, v33
	v_rcp_f32_e32 v34, v34
	v_rcp_f32_e32 v35, v35
	s_barrier
	v_pk_mul_f32 v[32:33], v[36:37], v[32:33]
	v_pk_mul_f32 v[34:35], v[38:39], v[34:35]
	v_pk_mul_f32 v[32:33], v[52:53], v[32:33]
	v_pk_mul_f32 v[34:35], v[54:55], v[34:35]
	v_cvt_pk_bf16_f32 v32, v32, v33
	v_cvt_pk_bf16_f32 v33, v34, v35
	v_cndmask_b32_e64 v34, v48, v32, s[38:39]
	v_cndmask_b32_e64 v35, v49, v33, s[38:39]
	v_mov_b32_e32 v255, v34
	s_nop 1
	v_permlane32_swap_b32_e32 v34, v255
	s_nop 1
	v_mov_b32_dpp v34, v255 quad_perm:[0,1,2,3] row_mask:0x3 bank_mask:0xf
	v_mov_b32_e32 v255, v35
	s_nop 1
	v_permlane32_swap_b32_e32 v35, v255
	s_nop 1
	v_mov_b32_dpp v35, v255 quad_perm:[0,1,2,3] row_mask:0x3 bank_mask:0xf
	s_mov_b64 s[44:45], 0
	s_andn2_b64 vcc, exec, s[0:1]
	s_mov_b32 s2, s3
	v_cndmask_b32_e64 v38, v32, v34, s[38:39]
	v_cndmask_b32_e64 v39, v33, v35, s[38:39]
	v_lshlrev_b64 v[32:33], 1, v[134:135]
	v_cndmask_b32_e64 v37, v35, v49, s[38:39]
	v_cndmask_b32_e64 v36, v34, v48, s[38:39]
	v_lshl_add_u64 v[34:35], v[136:137], 0, v[32:33]
	global_store_dwordx4 v[34:35], v[36:39], off
	s_nop 1
	v_mul_f32_e32 v36, 0xbfb8aa3b, v40
	v_mul_f32_e32 v37, 0xbfb8aa3b, v41
	v_mul_f32_e32 v38, 0xbfb8aa3b, v42
	v_mul_f32_e32 v39, 0xbfb8aa3b, v43
	v_exp_f32_e32 v36, v36
	v_exp_f32_e32 v37, v37
	v_exp_f32_e32 v38, v38
	v_exp_f32_e32 v39, v39
	v_add_f32_e32 v36, 1.0, v36
	v_add_f32_e32 v37, 1.0, v37
	v_add_f32_e32 v38, 1.0, v38
	v_add_f32_e32 v39, 1.0, v39
	v_rcp_f32_e32 v36, v36
	v_rcp_f32_e32 v37, v37
	v_rcp_f32_e32 v38, v38
	v_rcp_f32_e32 v39, v39
	v_pk_mul_f32 v[36:37], v[40:41], v[36:37]
	v_pk_mul_f32 v[36:37], v[56:57], v[36:37]
	v_pk_mul_f32 v[38:39], v[42:43], v[38:39]
	v_cvt_pk_bf16_f32 v40, v36, v37
	v_pk_mul_f32 v[38:39], v[58:59], v[38:39]
	v_mul_f32_e32 v36, 0xbfb8aa3b, v44
	v_cvt_pk_bf16_f32 v41, v38, v39
	v_mul_f32_e32 v37, 0xbfb8aa3b, v45
	v_mul_f32_e32 v38, 0xbfb8aa3b, v46
	v_mul_f32_e32 v39, 0xbfb8aa3b, v47
	v_exp_f32_e32 v36, v36
	v_exp_f32_e32 v37, v37
	v_exp_f32_e32 v38, v38
	v_exp_f32_e32 v39, v39
	v_add_f32_e32 v36, 1.0, v36
	v_add_f32_e32 v37, 1.0, v37
	v_add_f32_e32 v38, 1.0, v38
	v_add_f32_e32 v39, 1.0, v39
	v_rcp_f32_e32 v36, v36
	v_rcp_f32_e32 v37, v37
	v_rcp_f32_e32 v38, v38
	v_rcp_f32_e32 v39, v39
	v_pk_mul_f32 v[36:37], v[44:45], v[36:37]
	v_pk_mul_f32 v[36:37], v[60:61], v[36:37]
	v_pk_mul_f32 v[38:39], v[46:47], v[38:39]
	v_cvt_pk_bf16_f32 v36, v36, v37
	v_pk_mul_f32 v[38:39], v[62:63], v[38:39]
	v_cvt_pk_bf16_f32 v37, v38, v39
	v_cndmask_b32_e64 v38, v40, v36, s[38:39]
	v_cndmask_b32_e64 v39, v41, v37, s[38:39]
	v_mov_b32_e32 v42, v38
	v_mov_b32_e32 v255, v38
	s_nop 1
	v_permlane32_swap_b32_e32 v42, v255
	s_nop 1
	v_mov_b32_dpp v42, v255 quad_perm:[0,1,2,3] row_mask:0x3 bank_mask:0xf
	v_mov_b32_e32 v43, v39
	v_mov_b32_e32 v255, v39
	s_nop 1
	v_permlane32_swap_b32_e32 v43, v255
	s_nop 1
	v_mov_b32_dpp v43, v255 quad_perm:[0,1,2,3] row_mask:0x3 bank_mask:0xf
	v_cndmask_b32_e64 v38, v36, v42, s[38:39]
	v_cndmask_b32_e64 v39, v37, v43, s[38:39]
	v_cndmask_b32_e64 v37, v43, v41, s[38:39]
	v_cndmask_b32_e64 v36, v42, v40, s[38:39]
	global_store_dwordx4 v[34:35], v[36:39], off offset:32
	v_or_b32_e32 v34, 32, v132
	v_mad_i64_i32 v[34:35], s[6:7], v34, s18, v[98:99]
	v_mul_f32_e32 v36, 0xbfb8aa3b, v0
	v_mul_f32_e32 v37, 0xbfb8aa3b, v1
	v_exp_f32_e32 v36, v36
	v_exp_f32_e32 v37, v37
	v_add_f32_e32 v36, 1.0, v36
	v_add_f32_e32 v37, 1.0, v37
	v_rcp_f32_e32 v36, v36
	v_rcp_f32_e32 v37, v37
	s_nop 0
	v_pk_mul_f32 v[0:1], v[0:1], v[36:37]
	v_pk_mul_f32 v[0:1], v[16:17], v[0:1]
	v_mul_f32_e32 v16, 0xbfb8aa3b, v2
	v_mul_f32_e32 v17, 0xbfb8aa3b, v3
	v_exp_f32_e32 v16, v16
	v_exp_f32_e32 v17, v17
	v_add_f32_e32 v16, 1.0, v16
	v_add_f32_e32 v17, 1.0, v17
	v_rcp_f32_e32 v16, v16
	v_rcp_f32_e32 v17, v17
	s_nop 0
	v_pk_mul_f32 v[2:3], v[2:3], v[16:17]
	v_pk_mul_f32 v[2:3], v[18:19], v[2:3]
	v_cvt_pk_bf16_f32 v16, v0, v1
	v_cvt_pk_bf16_f32 v17, v2, v3
	v_mul_f32_e32 v0, 0xbfb8aa3b, v4
	v_mul_f32_e32 v1, 0xbfb8aa3b, v5
	v_mul_f32_e32 v2, 0xbfb8aa3b, v6
	v_mul_f32_e32 v3, 0xbfb8aa3b, v7
	v_exp_f32_e32 v0, v0
	v_exp_f32_e32 v1, v1
	v_exp_f32_e32 v2, v2
	v_exp_f32_e32 v3, v3
	v_add_f32_e32 v0, 1.0, v0
	v_add_f32_e32 v1, 1.0, v1
	v_add_f32_e32 v2, 1.0, v2
	v_add_f32_e32 v3, 1.0, v3
	v_rcp_f32_e32 v0, v0
	v_rcp_f32_e32 v1, v1
	v_rcp_f32_e32 v2, v2
	v_rcp_f32_e32 v3, v3
	v_pk_mul_f32 v[0:1], v[4:5], v[0:1]
	v_pk_mul_f32 v[0:1], v[20:21], v[0:1]
	v_pk_mul_f32 v[2:3], v[6:7], v[2:3]
	v_cvt_pk_bf16_f32 v0, v0, v1
	v_pk_mul_f32 v[2:3], v[22:23], v[2:3]
	v_cvt_pk_bf16_f32 v1, v2, v3
	v_cndmask_b32_e64 v2, v16, v0, s[38:39]
	v_cndmask_b32_e64 v3, v17, v1, s[38:39]
	v_mov_b32_e32 v255, v2
	s_nop 1
	v_permlane32_swap_b32_e32 v2, v255
	s_nop 1
	v_mov_b32_dpp v2, v255 quad_perm:[0,1,2,3] row_mask:0x3 bank_mask:0xf
	v_mov_b32_e32 v255, v3
	s_nop 1
	v_permlane32_swap_b32_e32 v3, v255
	s_nop 1
	v_mov_b32_dpp v3, v255 quad_perm:[0,1,2,3] row_mask:0x3 bank_mask:0xf
	v_cndmask_b32_e64 v4, v0, v2, s[38:39]
	v_cndmask_b32_e64 v5, v1, v3, s[38:39]
	v_cndmask_b32_e64 v3, v3, v17, s[38:39]
	v_cndmask_b32_e64 v2, v2, v16, s[38:39]
	v_lshl_add_u64 v[0:1], v[34:35], 0, v[32:33]
	global_store_dwordx4 v[0:1], v[2:5], off
	s_nop 1
	v_mul_f32_e32 v2, 0xbfb8aa3b, v8
	v_mul_f32_e32 v3, 0xbfb8aa3b, v9
	v_mul_f32_e32 v4, 0xbfb8aa3b, v10
	v_mul_f32_e32 v5, 0xbfb8aa3b, v11
	v_exp_f32_e32 v2, v2
	v_exp_f32_e32 v3, v3
	v_exp_f32_e32 v4, v4
	v_exp_f32_e32 v5, v5
	v_add_f32_e32 v2, 1.0, v2
	v_add_f32_e32 v3, 1.0, v3
	v_add_f32_e32 v4, 1.0, v4
	v_add_f32_e32 v5, 1.0, v5
	v_rcp_f32_e32 v2, v2
	v_rcp_f32_e32 v3, v3
	v_rcp_f32_e32 v4, v4
	v_rcp_f32_e32 v5, v5
	v_pk_mul_f32 v[2:3], v[8:9], v[2:3]
	v_pk_mul_f32 v[2:3], v[24:25], v[2:3]
	v_pk_mul_f32 v[4:5], v[10:11], v[4:5]
	v_cvt_pk_bf16_f32 v6, v2, v3
	v_pk_mul_f32 v[4:5], v[26:27], v[4:5]
	v_mul_f32_e32 v2, 0xbfb8aa3b, v12
	v_cvt_pk_bf16_f32 v7, v4, v5
	v_mul_f32_e32 v3, 0xbfb8aa3b, v13
	v_mul_f32_e32 v4, 0xbfb8aa3b, v14
	v_mul_f32_e32 v5, 0xbfb8aa3b, v15
	v_exp_f32_e32 v2, v2
	v_exp_f32_e32 v3, v3
	v_exp_f32_e32 v4, v4
	v_exp_f32_e32 v5, v5
	v_add_f32_e32 v2, 1.0, v2
	v_add_f32_e32 v3, 1.0, v3
	v_add_f32_e32 v4, 1.0, v4
	v_add_f32_e32 v5, 1.0, v5
	v_rcp_f32_e32 v2, v2
	v_rcp_f32_e32 v3, v3
	v_rcp_f32_e32 v4, v4
	v_rcp_f32_e32 v5, v5
	v_pk_mul_f32 v[2:3], v[12:13], v[2:3]
	v_pk_mul_f32 v[2:3], v[28:29], v[2:3]
	v_pk_mul_f32 v[4:5], v[14:15], v[4:5]
	v_cvt_pk_bf16_f32 v2, v2, v3
	v_pk_mul_f32 v[4:5], v[30:31], v[4:5]
	v_cvt_pk_bf16_f32 v3, v4, v5
	v_cndmask_b32_e64 v4, v6, v2, s[38:39]
	v_cndmask_b32_e64 v5, v7, v3, s[38:39]
	v_mov_b32_e32 v8, v4
	v_mov_b32_e32 v255, v4
	s_nop 1
	v_permlane32_swap_b32_e32 v8, v255
	s_nop 1
	v_mov_b32_dpp v8, v255 quad_perm:[0,1,2,3] row_mask:0x3 bank_mask:0xf
	v_mov_b32_e32 v9, v5
	v_mov_b32_e32 v255, v5
	s_nop 1
	v_permlane32_swap_b32_e32 v9, v255
	s_nop 1
	v_mov_b32_dpp v9, v255 quad_perm:[0,1,2,3] row_mask:0x3 bank_mask:0xf
	v_cndmask_b32_e64 v4, v2, v8, s[38:39]
	v_cndmask_b32_e64 v5, v3, v9, s[38:39]
	v_cndmask_b32_e64 v3, v9, v7, s[38:39]
	v_cndmask_b32_e64 v2, v8, v6, s[38:39]
	global_store_dwordx4 v[0:1], v[2:5], off offset:32
	s_cbranch_vccz .LBB0_274

.LBB0_268:
	s_add_u32 s4, s82, s40
	s_addc_u32 s7, s83, s41
	s_and_b64 s[10:11], s[12:13], exec
	s_cselect_b32 s10, s4, 0
	v_readlane_b32 s4, v251, 58
	s_cselect_b32 s11, s7, 0
	s_add_u32 s4, s4, s42
	v_readlane_b32 s7, v251, 59
	s_addc_u32 s7, s7, s43
	s_and_b64 s[40:41], s[12:13], exec
	s_cselect_b32 s41, s7, 0
	s_cselect_b32 s40, s4, 0
	v_lshl_add_u64 v[4:5], s[10:11], 0, v[0:1]
	v_lshl_add_u64 v[0:1], s[40:41], 0, v[0:1]
	v_lshl_add_u64 v[146:147], v[0:1], 0, v[96:97]
	v_lshrrev_b32_e32 v0, 1, v2
	v_and_b32_e32 v1, 31, v2
	v_and_or_b32 v1, v0, s81, v1
	v_lshrrev_b32_e32 v0, 2, v2
	v_and_b32_e32 v0, 8, v0
	v_lshl_add_u64 v[148:149], v[4:5], 0, v[96:97]
	v_mad_u64_u32 v[4:5], s[10:11], v1, s84, v[0:1]
	v_and_b32_e32 v1, 0x5f, v2
	v_mad_u32_u24 v0, v1, s84, v0
	v_lshl_add_u32 v176, v4, 1, 0
	v_lshl_add_u32 v96, v0, 1, 0
	v_add_u32_e32 v177, 0xd800, v175
	s_setprio 1
	ds_read_b128 v[212:215], v96 offset:36864
	ds_read_b128 v[216:219], v176
	ds_read_b128 v[220:223], v176 offset:4608
	ds_read_b128 v[224:227], v96 offset:36896
	ds_read_b128 v[228:231], v176 offset:32
	ds_read_b128 v[244:247], v176 offset:4640
	ds_read_b128 v[252:255], v96 offset:41472
	s_waitcnt lgkmcnt(5)
	v_mfma_f32_32x32x16_bf16 v[32:47], v[212:215], v[216:219], 0
	s_waitcnt lgkmcnt(4)
	v_mfma_f32_32x32x16_bf16 v[0:15], v[212:215], v[220:223], 0
	ds_read_b128 v[212:215], v96 offset:41504
	s_waitcnt lgkmcnt(3)
	v_mfma_f32_32x32x16_bf16 v[32:47], v[224:227], v[228:231], v[32:47]
	s_waitcnt lgkmcnt(2)
	v_mfma_f32_32x32x16_bf16 v[0:15], v[224:227], v[244:247], v[0:15]
	ds_read_b128 v[224:227], v96 offset:36928
	s_waitcnt lgkmcnt(2)
	v_mfma_f32_32x32x16_bf16 v[48:63], v[252:255], v[216:219], 0
	ds_read_b128 v[216:219], v176 offset:64
	v_mfma_f32_32x32x16_bf16 v[16:31], v[252:255], v[220:223], 0
	ds_read_b128 v[252:255], v176 offset:4672
	ds_read_b128 v[220:223], v96 offset:41536
	s_waitcnt lgkmcnt(4)
	v_mfma_f32_32x32x16_bf16 v[48:63], v[212:215], v[228:231], v[48:63]
	ds_read_b128 v[228:231], v96 offset:36960
	v_mfma_f32_32x32x16_bf16 v[16:31], v[212:215], v[244:247], v[16:31]
	ds_read_b128 v[212:215], v176 offset:96
	ds_read_b128 v[244:247], v176 offset:4704
	s_waitcnt lgkmcnt(5)
	v_mfma_f32_32x32x16_bf16 v[32:47], v[224:227], v[216:219], v[32:47]
	s_mov_b32 s4, 0x10000
	v_add_co_u32_e32 v154, vcc, s4, v152
	s_mov_b32 s7, 0x20000
	s_nop 0
	v_addc_co_u32_e32 v155, vcc, 0, v153, vcc
	v_add_co_u32_e32 v156, vcc, s7, v152
	s_mov_b32 s9, 0x30000
	s_nop 0
	s_waitcnt lgkmcnt(4)
	v_mfma_f32_32x32x16_bf16 v[0:15], v[224:227], v[252:255], v[0:15]
	ds_read_b128 v[224:227], v96 offset:41568
	v_addc_co_u32_e32 v157, vcc, 0, v153, vcc
	v_add_co_u32_e32 v158, vcc, s9, v152
	s_waitcnt vmcnt(11)
	ds_write_b128 v175, v[100:103] offset:18432
	s_waitcnt vmcnt(10)
	ds_write_b128 v175, v[104:107] offset:23040
	s_waitcnt lgkmcnt(6)
	v_mfma_f32_32x32x16_bf16 v[48:63], v[220:223], v[216:219], v[48:63]
	s_waitcnt vmcnt(9)
	ds_write_b128 v175, v[108:111] offset:27648
	s_waitcnt vmcnt(8)
	ds_write_b128 v175, v[112:115] offset:32256
	v_mfma_f32_32x32x16_bf16 v[16:31], v[220:223], v[252:255], v[16:31]
	s_waitcnt vmcnt(7)
	ds_write_b128 v175, v[116:119] offset:55296
	s_waitcnt vmcnt(6)
	ds_write_b128 v175, v[124:127] offset:59904
	s_waitcnt vmcnt(5)
	ds_write_b128 v175, v[120:123] offset:64512
	s_waitcnt lgkmcnt(9)
	v_mfma_f32_32x32x16_bf16 v[32:47], v[228:231], v[212:215], v[32:47]
	s_waitcnt vmcnt(4)
	ds_write_b128 v177, v[128:131] offset:13824
	v_addc_co_u32_e32 v159, vcc, 0, v153, vcc
	v_add_co_u32_e32 v160, vcc, s4, v150
	s_waitcnt lgkmcnt(9)
	v_mfma_f32_32x32x16_bf16 v[0:15], v[228:231], v[244:247], v[0:15]
	global_load_dwordx4 v[98:101], v[152:153], off offset:384
	global_load_dwordx4 v[102:105], v[154:155], off offset:384
	v_addc_co_u32_e32 v161, vcc, 0, v151, vcc
	v_add_co_u32_e32 v170, vcc, s7, v150
	global_load_dwordx4 v[106:109], v[156:157], off offset:384
	s_waitcnt lgkmcnt(8)
	v_mfma_f32_32x32x16_bf16 v[48:63], v[224:227], v[212:215], v[48:63]
	s_nop 0
	v_addc_co_u32_e32 v171, vcc, 0, v151, vcc
	v_add_co_u32_e32 v172, vcc, s9, v150
	global_load_dwordx4 v[110:113], v[158:159], off offset:384
	global_load_dwordx4 v[114:117], v[150:151], off offset:384
	v_mfma_f32_32x32x16_bf16 v[16:31], v[224:227], v[244:247], v[16:31]
	v_addc_co_u32_e32 v173, vcc, 0, v151, vcc
	global_load_dwordx4 v[118:121], v[160:161], off offset:384
	global_load_dwordx4 v[122:125], v[170:171], off offset:384
	global_load_dwordx4 v[130:133], v[172:173], off offset:384
	s_setprio 0
	s_waitcnt lgkmcnt(0)
	s_barrier
	s_setprio 1
	ds_read_b128 v[212:215], v96 offset:55296
	ds_read_b128 v[216:219], v176 offset:18432
	ds_read_b128 v[220:223], v176 offset:23040
	ds_read_b128 v[224:227], v96 offset:59904
	ds_read_b128 v[228:231], v96 offset:55328
	ds_read_b128 v[244:247], v176 offset:18464
	ds_read_b128 v[252:255], v176 offset:23072
	s_waitcnt lgkmcnt(5)
	v_mfma_f32_32x32x16_bf16 v[32:47], v[212:215], v[216:219], v[32:47]
	s_waitcnt lgkmcnt(4)
	v_mfma_f32_32x32x16_bf16 v[0:15], v[212:215], v[220:223], v[0:15]
	ds_read_b128 v[212:215], v96 offset:59936
	s_waitcnt lgkmcnt(4)
	v_mfma_f32_32x32x16_bf16 v[48:63], v[224:227], v[216:219], v[48:63]
	ds_read_b128 v[216:219], v96 offset:55360
	v_mfma_f32_32x32x16_bf16 v[16:31], v[224:227], v[220:223], v[16:31]
	ds_read_b128 v[224:227], v176 offset:18496
	ds_read_b128 v[220:223], v176 offset:23104
	s_waitcnt lgkmcnt(5)
	v_mfma_f32_32x32x16_bf16 v[32:47], v[228:231], v[244:247], v[32:47]
	s_waitcnt lgkmcnt(4)
	v_mfma_f32_32x32x16_bf16 v[0:15], v[228:231], v[252:255], v[0:15]
	ds_read_b128 v[228:231], v96 offset:59968
	s_waitcnt lgkmcnt(4)
	v_mfma_f32_32x32x16_bf16 v[48:63], v[212:215], v[244:247], v[48:63]
	ds_read_b128 v[244:247], v96 offset:55392
	v_mfma_f32_32x32x16_bf16 v[16:31], v[212:215], v[252:255], v[16:31]
	ds_read_b128 v[212:215], v176 offset:18528
	ds_read_b128 v[252:255], v176 offset:23136
	s_waitcnt lgkmcnt(5)
	v_mfma_f32_32x32x16_bf16 v[32:47], v[216:219], v[224:227], v[32:47]
	s_waitcnt vmcnt(15)
	ds_write_b128 v175, v[64:67]
	global_load_dwordx4 v[64:67], v[152:153], off offset:512
	s_waitcnt lgkmcnt(5)
	v_mfma_f32_32x32x16_bf16 v[0:15], v[216:219], v[220:223], v[0:15]
	ds_read_b128 v[216:219], v96 offset:60000
	s_waitcnt vmcnt(15)
	ds_write_b128 v175, v[68:71] offset:4608
	s_waitcnt vmcnt(14)
	ds_write_b128 v175, v[72:75] offset:9216
	s_waitcnt lgkmcnt(7)
	v_mfma_f32_32x32x16_bf16 v[48:63], v[228:231], v[224:227], v[48:63]
	global_load_dwordx4 v[72:75], v[154:155], off offset:512
	s_waitcnt vmcnt(14)
	ds_write_b128 v175, v[76:79] offset:13824
	v_mfma_f32_32x32x16_bf16 v[16:31], v[228:231], v[220:223], v[16:31]
	global_load_dwordx4 v[76:79], v[156:157], off offset:512
	s_waitcnt vmcnt(14)
	ds_write_b128 v175, v[80:83] offset:36864
	s_waitcnt lgkmcnt(7)
	v_mfma_f32_32x32x16_bf16 v[32:47], v[244:247], v[212:215], v[32:47]
	global_load_dwordx4 v[80:83], v[158:159], off offset:512
	global_load_dwordx4 v[126:129], v[150:151], off offset:512
	s_waitcnt lgkmcnt(6)
	v_mfma_f32_32x32x16_bf16 v[0:15], v[244:247], v[252:255], v[0:15]
	s_waitcnt vmcnt(15)
	ds_write_b128 v175, v[84:87] offset:41472
	global_load_dwordx4 v[134:137], v[160:161], off offset:512
	s_waitcnt lgkmcnt(5)
	v_mfma_f32_32x32x16_bf16 v[48:63], v[216:219], v[212:215], v[48:63]
	s_waitcnt vmcnt(15)
	ds_write_b128 v175, v[88:91] offset:46080
	global_load_dwordx4 v[138:141], v[170:171], off offset:512
	v_mfma_f32_32x32x16_bf16 v[16:31], v[216:219], v[252:255], v[16:31]
	s_waitcnt vmcnt(15)
	ds_write_b128 v175, v[92:95] offset:50688
	global_load_dwordx4 v[142:145], v[172:173], off offset:512
	s_setprio 0
	s_waitcnt lgkmcnt(0)
	s_barrier
	s_setprio 1
	ds_read_b128 v[212:215], v96 offset:36864
	ds_read_b128 v[216:219], v176
	ds_read_b128 v[220:223], v176 offset:4608
	ds_read_b128 v[224:227], v96 offset:41472
	ds_read_b128 v[228:231], v96 offset:36896
	ds_read_b128 v[244:247], v176 offset:32
	ds_read_b128 v[252:255], v176 offset:4640
	s_waitcnt lgkmcnt(5)
	v_mfma_f32_32x32x16_bf16 v[32:47], v[212:215], v[216:219], v[32:47]
	s_waitcnt lgkmcnt(4)
	v_mfma_f32_32x32x16_bf16 v[0:15], v[212:215], v[220:223], v[0:15]
	ds_read_b128 v[212:215], v96 offset:41504
	s_waitcnt lgkmcnt(4)
	v_mfma_f32_32x32x16_bf16 v[48:63], v[224:227], v[216:219], v[48:63]
	ds_read_b128 v[216:219], v96 offset:36928
	v_mfma_f32_32x32x16_bf16 v[16:31], v[224:227], v[220:223], v[16:31]
	ds_read_b128 v[224:227], v176 offset:64
	ds_read_b128 v[220:223], v176 offset:4672
	s_waitcnt lgkmcnt(5)
	v_mfma_f32_32x32x16_bf16 v[32:47], v[228:231], v[244:247], v[32:47]
	s_waitcnt lgkmcnt(4)
	v_mfma_f32_32x32x16_bf16 v[0:15], v[228:231], v[252:255], v[0:15]
	ds_read_b128 v[228:231], v96 offset:41536
	s_waitcnt lgkmcnt(4)
	v_mfma_f32_32x32x16_bf16 v[48:63], v[212:215], v[244:247], v[48:63]
	ds_read_b128 v[244:247], v96 offset:36960
	v_mfma_f32_32x32x16_bf16 v[16:31], v[212:215], v[252:255], v[16:31]
	ds_read_b128 v[212:215], v176 offset:96
	ds_read_b128 v[252:255], v176 offset:4704
	s_waitcnt lgkmcnt(5)
	v_mfma_f32_32x32x16_bf16 v[32:47], v[216:219], v[224:227], v[32:47]
	s_waitcnt vmcnt(15)
	ds_write_b128 v175, v[98:101] offset:18432
	global_load_dwordx4 v[68:71], v[152:153], off offset:640
	s_waitcnt lgkmcnt(5)
	v_mfma_f32_32x32x16_bf16 v[0:15], v[216:219], v[220:223], v[0:15]
	ds_read_b128 v[216:219], v96 offset:41568
	s_waitcnt vmcnt(15)
	ds_write_b128 v175, v[102:105] offset:23040
	global_load_dwordx4 v[84:87], v[154:155], off offset:640
	s_waitcnt lgkmcnt(6)
	v_mfma_f32_32x32x16_bf16 v[48:63], v[228:231], v[224:227], v[48:63]
	s_waitcnt vmcnt(15)
	ds_write_b128 v175, v[106:109] offset:27648
	global_load_dwordx4 v[88:91], v[156:157], off offset:640
	v_mfma_f32_32x32x16_bf16 v[16:31], v[228:231], v[220:223], v[16:31]
	s_waitcnt vmcnt(15)
	ds_write_b128 v175, v[110:113] offset:32256
	global_load_dwordx4 v[92:95], v[158:159], off offset:640
	s_waitcnt lgkmcnt(6)
	v_mfma_f32_32x32x16_bf16 v[32:47], v[244:247], v[212:215], v[32:47]
	s_waitcnt vmcnt(15)
	ds_write_b128 v175, v[114:117] offset:55296
	global_load_dwordx4 v[98:101], v[150:151], off offset:640
	s_waitcnt lgkmcnt(6)
	v_mfma_f32_32x32x16_bf16 v[0:15], v[244:247], v[252:255], v[0:15]
	s_waitcnt vmcnt(15)
	ds_write_b128 v175, v[118:121] offset:59904
	global_load_dwordx4 v[106:109], v[160:161], off offset:640
	s_waitcnt lgkmcnt(5)
	v_mfma_f32_32x32x16_bf16 v[48:63], v[216:219], v[212:215], v[48:63]
	s_waitcnt vmcnt(15)
	ds_write_b128 v175, v[122:125] offset:64512
	global_load_dwordx4 v[110:113], v[170:171], off offset:640
	v_mfma_f32_32x32x16_bf16 v[16:31], v[216:219], v[252:255], v[16:31]
	s_waitcnt vmcnt(15)
	ds_write_b128 v177, v[130:133] offset:13824
	global_load_dwordx4 v[114:117], v[172:173], off offset:640
	s_setprio 0
	s_waitcnt lgkmcnt(0)
	s_barrier
	s_setprio 1
	ds_read_b128 v[212:215], v96 offset:55296
	ds_read_b128 v[216:219], v176 offset:18432
	ds_read_b128 v[220:223], v176 offset:23040
	ds_read_b128 v[224:227], v96 offset:59904
	ds_read_b128 v[228:231], v96 offset:55328
	ds_read_b128 v[244:247], v176 offset:18464
	ds_read_b128 v[252:255], v176 offset:23072
	s_waitcnt lgkmcnt(5)
	v_mfma_f32_32x32x16_bf16 v[32:47], v[212:215], v[216:219], v[32:47]
	s_waitcnt lgkmcnt(4)
	v_mfma_f32_32x32x16_bf16 v[0:15], v[212:215], v[220:223], v[0:15]
	ds_read_b128 v[212:215], v96 offset:59936
	s_waitcnt lgkmcnt(4)
	v_mfma_f32_32x32x16_bf16 v[48:63], v[224:227], v[216:219], v[48:63]
	ds_read_b128 v[216:219], v96 offset:55360
	v_mfma_f32_32x32x16_bf16 v[16:31], v[224:227], v[220:223], v[16:31]
	ds_read_b128 v[224:227], v176 offset:18496
	ds_read_b128 v[220:223], v176 offset:23104
	s_waitcnt lgkmcnt(5)
	v_mfma_f32_32x32x16_bf16 v[32:47], v[228:231], v[244:247], v[32:47]
	s_waitcnt lgkmcnt(4)
	v_mfma_f32_32x32x16_bf16 v[0:15], v[228:231], v[252:255], v[0:15]
	ds_read_b128 v[228:231], v96 offset:59968
	s_waitcnt lgkmcnt(4)
	v_mfma_f32_32x32x16_bf16 v[48:63], v[212:215], v[244:247], v[48:63]
	ds_read_b128 v[244:247], v96 offset:55392
	v_mfma_f32_32x32x16_bf16 v[16:31], v[212:215], v[252:255], v[16:31]
	ds_read_b128 v[212:215], v176 offset:18528
	ds_read_b128 v[252:255], v176 offset:23136
	s_waitcnt lgkmcnt(5)
	v_mfma_f32_32x32x16_bf16 v[32:47], v[216:219], v[224:227], v[32:47]
	s_waitcnt vmcnt(15)
	ds_write_b128 v175, v[64:67]
	global_load_dwordx4 v[64:67], v[152:153], off offset:768
	s_waitcnt lgkmcnt(5)
	v_mfma_f32_32x32x16_bf16 v[0:15], v[216:219], v[220:223], v[0:15]
	ds_read_b128 v[216:219], v96 offset:60000
	s_waitcnt vmcnt(15)
	ds_write_b128 v175, v[72:75] offset:4608
	global_load_dwordx4 v[72:75], v[154:155], off offset:768
	s_waitcnt lgkmcnt(6)
	v_mfma_f32_32x32x16_bf16 v[48:63], v[228:231], v[224:227], v[48:63]
	s_waitcnt vmcnt(15)
	ds_write_b128 v175, v[76:79] offset:9216
	global_load_dwordx4 v[76:79], v[156:157], off offset:768
	v_mfma_f32_32x32x16_bf16 v[16:31], v[228:231], v[220:223], v[16:31]
	s_waitcnt vmcnt(15)
	ds_write_b128 v175, v[80:83] offset:13824
	global_load_dwordx4 v[80:83], v[158:159], off offset:768
	s_waitcnt lgkmcnt(6)
	v_mfma_f32_32x32x16_bf16 v[32:47], v[244:247], v[212:215], v[32:47]
	s_waitcnt vmcnt(15)
	ds_write_b128 v175, v[126:129] offset:36864
	global_load_dwordx4 v[102:105], v[150:151], off offset:768
	s_waitcnt lgkmcnt(6)
	v_mfma_f32_32x32x16_bf16 v[0:15], v[244:247], v[252:255], v[0:15]
	s_waitcnt vmcnt(15)
	ds_write_b128 v175, v[134:137] offset:41472
	global_load_dwordx4 v[118:121], v[160:161], off offset:768
	s_waitcnt lgkmcnt(5)
	v_mfma_f32_32x32x16_bf16 v[48:63], v[216:219], v[212:215], v[48:63]
	s_waitcnt vmcnt(15)
	ds_write_b128 v175, v[138:141] offset:46080
	global_load_dwordx4 v[122:125], v[170:171], off offset:768
	v_mfma_f32_32x32x16_bf16 v[16:31], v[216:219], v[252:255], v[16:31]
	s_waitcnt vmcnt(15)
	ds_write_b128 v175, v[142:145] offset:50688
	global_load_dwordx4 v[126:129], v[172:173], off offset:768
	s_setprio 0
	s_waitcnt lgkmcnt(0)
	s_barrier
	s_setprio 1
	ds_read_b128 v[212:215], v96 offset:36864
	ds_read_b128 v[216:219], v176
	ds_read_b128 v[220:223], v176 offset:4608
	ds_read_b128 v[224:227], v96 offset:41472
	ds_read_b128 v[228:231], v96 offset:36896
	ds_read_b128 v[244:247], v176 offset:32
	ds_read_b128 v[252:255], v176 offset:4640
	s_waitcnt lgkmcnt(5)
	v_mfma_f32_32x32x16_bf16 v[32:47], v[212:215], v[216:219], v[32:47]
	s_waitcnt lgkmcnt(4)
	v_mfma_f32_32x32x16_bf16 v[0:15], v[212:215], v[220:223], v[0:15]
	ds_read_b128 v[212:215], v96 offset:41504
	s_waitcnt lgkmcnt(4)
	v_mfma_f32_32x32x16_bf16 v[48:63], v[224:227], v[216:219], v[48:63]
	ds_read_b128 v[216:219], v96 offset:36928
	v_mfma_f32_32x32x16_bf16 v[16:31], v[224:227], v[220:223], v[16:31]
	ds_read_b128 v[224:227], v176 offset:64
	ds_read_b128 v[220:223], v176 offset:4672
	s_waitcnt lgkmcnt(5)
	v_mfma_f32_32x32x16_bf16 v[32:47], v[228:231], v[244:247], v[32:47]
	s_waitcnt lgkmcnt(4)
	v_mfma_f32_32x32x16_bf16 v[0:15], v[228:231], v[252:255], v[0:15]
	ds_read_b128 v[228:231], v96 offset:41536
	s_waitcnt lgkmcnt(4)
	v_mfma_f32_32x32x16_bf16 v[48:63], v[212:215], v[244:247], v[48:63]
	ds_read_b128 v[244:247], v96 offset:36960
	v_mfma_f32_32x32x16_bf16 v[16:31], v[212:215], v[252:255], v[16:31]
	ds_read_b128 v[212:215], v176 offset:96
	ds_read_b128 v[252:255], v176 offset:4704
	s_waitcnt lgkmcnt(5)
	v_mfma_f32_32x32x16_bf16 v[32:47], v[216:219], v[224:227], v[32:47]
	s_waitcnt vmcnt(15)
	ds_write_b128 v175, v[68:71] offset:18432
	global_load_dwordx4 v[68:71], v[152:153], off offset:896
	s_waitcnt lgkmcnt(5)
	v_mfma_f32_32x32x16_bf16 v[0:15], v[216:219], v[220:223], v[0:15]
	ds_read_b128 v[216:219], v96 offset:41568
	s_waitcnt vmcnt(15)
	ds_write_b128 v175, v[84:87] offset:23040
	global_load_dwordx4 v[84:87], v[154:155], off offset:896
	s_waitcnt lgkmcnt(6)
	v_mfma_f32_32x32x16_bf16 v[48:63], v[228:231], v[224:227], v[48:63]
	s_waitcnt vmcnt(15)
	ds_write_b128 v175, v[88:91] offset:27648
	global_load_dwordx4 v[88:91], v[156:157], off offset:896
	v_mfma_f32_32x32x16_bf16 v[16:31], v[228:231], v[220:223], v[16:31]
	s_waitcnt vmcnt(15)
	ds_write_b128 v175, v[92:95] offset:32256
	global_load_dwordx4 v[92:95], v[158:159], off offset:896
	s_waitcnt lgkmcnt(6)
	v_mfma_f32_32x32x16_bf16 v[32:47], v[244:247], v[212:215], v[32:47]
	s_waitcnt vmcnt(15)
	ds_write_b128 v175, v[98:101] offset:55296
	global_load_dwordx4 v[98:101], v[150:151], off offset:896
	s_waitcnt lgkmcnt(6)
	v_mfma_f32_32x32x16_bf16 v[0:15], v[244:247], v[252:255], v[0:15]
	s_waitcnt vmcnt(15)
	ds_write_b128 v175, v[106:109] offset:59904
	global_load_dwordx4 v[106:109], v[160:161], off offset:896
	s_waitcnt lgkmcnt(5)
	v_mfma_f32_32x32x16_bf16 v[48:63], v[216:219], v[212:215], v[48:63]
	s_waitcnt vmcnt(15)
	ds_write_b128 v175, v[110:113] offset:64512
	global_load_dwordx4 v[110:113], v[170:171], off offset:896
	v_mfma_f32_32x32x16_bf16 v[16:31], v[216:219], v[252:255], v[16:31]
	s_waitcnt vmcnt(15)
	ds_write_b128 v177, v[114:117] offset:13824
	global_load_dwordx4 v[114:117], v[172:173], off offset:896
	s_setprio 0
	s_waitcnt lgkmcnt(0)
	s_barrier
	s_setprio 1
	ds_read_b128 v[212:215], v96 offset:55296
	ds_read_b128 v[216:219], v176 offset:18432
	ds_read_b128 v[220:223], v176 offset:23040
	ds_read_b128 v[224:227], v96 offset:59904
	ds_read_b128 v[228:231], v96 offset:55328
	ds_read_b128 v[244:247], v176 offset:18464
	ds_read_b128 v[252:255], v176 offset:23072
	s_waitcnt lgkmcnt(5)
	v_mfma_f32_32x32x16_bf16 v[32:47], v[212:215], v[216:219], v[32:47]
	s_waitcnt lgkmcnt(4)
	v_mfma_f32_32x32x16_bf16 v[0:15], v[212:215], v[220:223], v[0:15]
	ds_read_b128 v[212:215], v96 offset:59936
	s_waitcnt lgkmcnt(4)
	v_mfma_f32_32x32x16_bf16 v[48:63], v[224:227], v[216:219], v[48:63]
	ds_read_b128 v[216:219], v96 offset:55360
	v_mfma_f32_32x32x16_bf16 v[16:31], v[224:227], v[220:223], v[16:31]
	ds_read_b128 v[224:227], v176 offset:18496
	ds_read_b128 v[220:223], v176 offset:23104
	s_waitcnt lgkmcnt(5)
	v_mfma_f32_32x32x16_bf16 v[32:47], v[228:231], v[244:247], v[32:47]
	s_waitcnt lgkmcnt(4)
	v_mfma_f32_32x32x16_bf16 v[0:15], v[228:231], v[252:255], v[0:15]
	ds_read_b128 v[228:231], v96 offset:59968
	s_waitcnt lgkmcnt(4)
	v_mfma_f32_32x32x16_bf16 v[48:63], v[212:215], v[244:247], v[48:63]
	ds_read_b128 v[244:247], v96 offset:55392
	v_mfma_f32_32x32x16_bf16 v[16:31], v[212:215], v[252:255], v[16:31]
	ds_read_b128 v[212:215], v176 offset:18528
	ds_read_b128 v[252:255], v176 offset:23136
	s_waitcnt lgkmcnt(5)
	v_mfma_f32_32x32x16_bf16 v[32:47], v[216:219], v[224:227], v[32:47]
	s_waitcnt vmcnt(15)
	ds_write_b128 v175, v[64:67]
	global_load_dwordx4 v[64:67], v[152:153], off offset:1024
	s_waitcnt lgkmcnt(5)
	v_mfma_f32_32x32x16_bf16 v[0:15], v[216:219], v[220:223], v[0:15]
	ds_read_b128 v[216:219], v96 offset:60000
	s_waitcnt vmcnt(15)
	ds_write_b128 v175, v[72:75] offset:4608
	global_load_dwordx4 v[72:75], v[154:155], off offset:1024
	s_waitcnt lgkmcnt(6)
	v_mfma_f32_32x32x16_bf16 v[48:63], v[228:231], v[224:227], v[48:63]
	s_waitcnt vmcnt(15)
	ds_write_b128 v175, v[76:79] offset:9216
	global_load_dwordx4 v[76:79], v[156:157], off offset:1024
	v_mfma_f32_32x32x16_bf16 v[16:31], v[228:231], v[220:223], v[16:31]
	s_waitcnt vmcnt(15)
	ds_write_b128 v175, v[80:83] offset:13824
	global_load_dwordx4 v[80:83], v[158:159], off offset:1024
	s_waitcnt lgkmcnt(6)
	v_mfma_f32_32x32x16_bf16 v[32:47], v[244:247], v[212:215], v[32:47]
	s_waitcnt vmcnt(15)
	ds_write_b128 v175, v[102:105] offset:36864
	global_load_dwordx4 v[102:105], v[150:151], off offset:1024
	s_waitcnt lgkmcnt(6)
	v_mfma_f32_32x32x16_bf16 v[0:15], v[244:247], v[252:255], v[0:15]
	s_waitcnt vmcnt(15)
	ds_write_b128 v175, v[118:121] offset:41472
	global_load_dwordx4 v[118:121], v[160:161], off offset:1024
	s_waitcnt lgkmcnt(5)
	v_mfma_f32_32x32x16_bf16 v[48:63], v[216:219], v[212:215], v[48:63]
	s_waitcnt vmcnt(15)
	ds_write_b128 v175, v[122:125] offset:46080
	global_load_dwordx4 v[122:125], v[170:171], off offset:1024
	v_mfma_f32_32x32x16_bf16 v[16:31], v[216:219], v[252:255], v[16:31]
	s_waitcnt vmcnt(15)
	ds_write_b128 v175, v[126:129] offset:50688
	global_load_dwordx4 v[126:129], v[172:173], off offset:1024
	s_setprio 0
	s_waitcnt lgkmcnt(0)
	s_barrier
	s_setprio 1
	ds_read_b128 v[212:215], v96 offset:36864
	ds_read_b128 v[216:219], v176
	ds_read_b128 v[220:223], v176 offset:4608
	ds_read_b128 v[224:227], v96 offset:41472
	ds_read_b128 v[228:231], v96 offset:36896
	ds_read_b128 v[244:247], v176 offset:32
	ds_read_b128 v[252:255], v176 offset:4640
	s_waitcnt lgkmcnt(5)
	v_mfma_f32_32x32x16_bf16 v[32:47], v[212:215], v[216:219], v[32:47]
	s_waitcnt lgkmcnt(4)
	v_mfma_f32_32x32x16_bf16 v[0:15], v[212:215], v[220:223], v[0:15]
	ds_read_b128 v[212:215], v96 offset:41504
	s_waitcnt lgkmcnt(4)
	v_mfma_f32_32x32x16_bf16 v[48:63], v[224:227], v[216:219], v[48:63]
	ds_read_b128 v[216:219], v96 offset:36928
	v_mfma_f32_32x32x16_bf16 v[16:31], v[224:227], v[220:223], v[16:31]
	ds_read_b128 v[224:227], v176 offset:64
	ds_read_b128 v[220:223], v176 offset:4672
	s_waitcnt lgkmcnt(5)
	v_mfma_f32_32x32x16_bf16 v[32:47], v[228:231], v[244:247], v[32:47]
	s_waitcnt lgkmcnt(4)
	v_mfma_f32_32x32x16_bf16 v[0:15], v[228:231], v[252:255], v[0:15]
	ds_read_b128 v[228:231], v96 offset:41536
	s_waitcnt lgkmcnt(4)
	v_mfma_f32_32x32x16_bf16 v[48:63], v[212:215], v[244:247], v[48:63]
	ds_read_b128 v[244:247], v96 offset:36960
	v_mfma_f32_32x32x16_bf16 v[16:31], v[212:215], v[252:255], v[16:31]
	ds_read_b128 v[212:215], v176 offset:96
	ds_read_b128 v[252:255], v176 offset:4704
	s_waitcnt lgkmcnt(5)
	v_mfma_f32_32x32x16_bf16 v[32:47], v[216:219], v[224:227], v[32:47]
	s_waitcnt vmcnt(15)
	ds_write_b128 v175, v[68:71] offset:18432
	global_load_dwordx4 v[68:71], v[152:153], off offset:1152
	s_waitcnt lgkmcnt(5)
	v_mfma_f32_32x32x16_bf16 v[0:15], v[216:219], v[220:223], v[0:15]
	ds_read_b128 v[216:219], v96 offset:41568
	s_waitcnt vmcnt(15)
	ds_write_b128 v175, v[84:87] offset:23040
	global_load_dwordx4 v[84:87], v[154:155], off offset:1152
	s_waitcnt lgkmcnt(6)
	v_mfma_f32_32x32x16_bf16 v[48:63], v[228:231], v[224:227], v[48:63]
	s_waitcnt vmcnt(15)
	ds_write_b128 v175, v[88:91] offset:27648
	global_load_dwordx4 v[88:91], v[156:157], off offset:1152
	v_mfma_f32_32x32x16_bf16 v[16:31], v[228:231], v[220:223], v[16:31]
	s_waitcnt vmcnt(15)
	ds_write_b128 v175, v[92:95] offset:32256
	global_load_dwordx4 v[92:95], v[158:159], off offset:1152
	s_waitcnt lgkmcnt(6)
	v_mfma_f32_32x32x16_bf16 v[32:47], v[244:247], v[212:215], v[32:47]
	s_waitcnt vmcnt(15)
	ds_write_b128 v175, v[98:101] offset:55296
	global_load_dwordx4 v[98:101], v[150:151], off offset:1152
	s_waitcnt lgkmcnt(6)
	v_mfma_f32_32x32x16_bf16 v[0:15], v[244:247], v[252:255], v[0:15]
	s_waitcnt vmcnt(15)
	ds_write_b128 v175, v[106:109] offset:59904
	global_load_dwordx4 v[106:109], v[160:161], off offset:1152
	s_waitcnt lgkmcnt(5)
	v_mfma_f32_32x32x16_bf16 v[48:63], v[216:219], v[212:215], v[48:63]
	s_waitcnt vmcnt(15)
	ds_write_b128 v175, v[110:113] offset:64512
	global_load_dwordx4 v[110:113], v[170:171], off offset:1152
	v_mfma_f32_32x32x16_bf16 v[16:31], v[216:219], v[252:255], v[16:31]
	s_waitcnt vmcnt(15)
	ds_write_b128 v177, v[114:117] offset:13824
	global_load_dwordx4 v[114:117], v[172:173], off offset:1152
	s_setprio 0
	s_waitcnt lgkmcnt(0)
	s_barrier
	s_setprio 1
	ds_read_b128 v[212:215], v96 offset:55296
	ds_read_b128 v[216:219], v176 offset:18432
	ds_read_b128 v[220:223], v176 offset:23040
	ds_read_b128 v[224:227], v96 offset:59904
	ds_read_b128 v[228:231], v96 offset:55328
	ds_read_b128 v[244:247], v176 offset:18464
	ds_read_b128 v[252:255], v176 offset:23072
	s_waitcnt lgkmcnt(5)
	v_mfma_f32_32x32x16_bf16 v[32:47], v[212:215], v[216:219], v[32:47]
	s_waitcnt lgkmcnt(4)
	v_mfma_f32_32x32x16_bf16 v[0:15], v[212:215], v[220:223], v[0:15]
	ds_read_b128 v[212:215], v96 offset:59936
	s_waitcnt lgkmcnt(4)
	v_mfma_f32_32x32x16_bf16 v[48:63], v[224:227], v[216:219], v[48:63]
	ds_read_b128 v[216:219], v96 offset:55360
	v_mfma_f32_32x32x16_bf16 v[16:31], v[224:227], v[220:223], v[16:31]
	ds_read_b128 v[224:227], v176 offset:18496
	ds_read_b128 v[220:223], v176 offset:23104
	s_waitcnt lgkmcnt(5)
	v_mfma_f32_32x32x16_bf16 v[32:47], v[228:231], v[244:247], v[32:47]
	s_waitcnt lgkmcnt(4)
	v_mfma_f32_32x32x16_bf16 v[0:15], v[228:231], v[252:255], v[0:15]
	ds_read_b128 v[228:231], v96 offset:59968
	s_waitcnt lgkmcnt(4)
	v_mfma_f32_32x32x16_bf16 v[48:63], v[212:215], v[244:247], v[48:63]
	ds_read_b128 v[244:247], v96 offset:55392
	v_mfma_f32_32x32x16_bf16 v[16:31], v[212:215], v[252:255], v[16:31]
	ds_read_b128 v[212:215], v176 offset:18528
	ds_read_b128 v[252:255], v176 offset:23136
	s_waitcnt lgkmcnt(5)
	v_mfma_f32_32x32x16_bf16 v[32:47], v[216:219], v[224:227], v[32:47]
	s_waitcnt vmcnt(15)
	ds_write_b128 v175, v[64:67]
	global_load_dwordx4 v[64:67], v[152:153], off offset:1280
	s_waitcnt lgkmcnt(5)
	v_mfma_f32_32x32x16_bf16 v[0:15], v[216:219], v[220:223], v[0:15]
	ds_read_b128 v[216:219], v96 offset:60000
	s_waitcnt vmcnt(15)
	ds_write_b128 v175, v[72:75] offset:4608
	global_load_dwordx4 v[72:75], v[154:155], off offset:1280
	s_waitcnt lgkmcnt(6)
	v_mfma_f32_32x32x16_bf16 v[48:63], v[228:231], v[224:227], v[48:63]
	s_waitcnt vmcnt(15)
	ds_write_b128 v175, v[76:79] offset:9216
	global_load_dwordx4 v[76:79], v[156:157], off offset:1280
	v_mfma_f32_32x32x16_bf16 v[16:31], v[228:231], v[220:223], v[16:31]
	s_waitcnt vmcnt(15)
	ds_write_b128 v175, v[80:83] offset:13824
	global_load_dwordx4 v[80:83], v[158:159], off offset:1280
	s_waitcnt lgkmcnt(6)
	v_mfma_f32_32x32x16_bf16 v[32:47], v[244:247], v[212:215], v[32:47]
	s_waitcnt vmcnt(15)
	ds_write_b128 v175, v[102:105] offset:36864
	global_load_dwordx4 v[102:105], v[150:151], off offset:1280
	s_waitcnt lgkmcnt(6)
	v_mfma_f32_32x32x16_bf16 v[0:15], v[244:247], v[252:255], v[0:15]
	s_waitcnt vmcnt(15)
	ds_write_b128 v175, v[118:121] offset:41472
	global_load_dwordx4 v[118:121], v[160:161], off offset:1280
	s_waitcnt lgkmcnt(5)
	v_mfma_f32_32x32x16_bf16 v[48:63], v[216:219], v[212:215], v[48:63]
	s_waitcnt vmcnt(15)
	ds_write_b128 v175, v[122:125] offset:46080
	global_load_dwordx4 v[122:125], v[170:171], off offset:1280
	v_mfma_f32_32x32x16_bf16 v[16:31], v[216:219], v[252:255], v[16:31]
	s_waitcnt vmcnt(15)
	ds_write_b128 v175, v[126:129] offset:50688
	global_load_dwordx4 v[126:129], v[172:173], off offset:1280
	s_setprio 0
	s_waitcnt lgkmcnt(0)
	s_barrier
	s_setprio 1
	ds_read_b128 v[212:215], v96 offset:36864
	ds_read_b128 v[216:219], v176
	ds_read_b128 v[220:223], v176 offset:4608
	ds_read_b128 v[224:227], v96 offset:41472
	ds_read_b128 v[228:231], v96 offset:36896
	ds_read_b128 v[244:247], v176 offset:32
	ds_read_b128 v[252:255], v176 offset:4640
	s_waitcnt lgkmcnt(5)
	v_mfma_f32_32x32x16_bf16 v[32:47], v[212:215], v[216:219], v[32:47]
	s_waitcnt lgkmcnt(4)
	v_mfma_f32_32x32x16_bf16 v[0:15], v[212:215], v[220:223], v[0:15]
	ds_read_b128 v[212:215], v96 offset:41504
	s_waitcnt lgkmcnt(4)
	v_mfma_f32_32x32x16_bf16 v[48:63], v[224:227], v[216:219], v[48:63]
	ds_read_b128 v[216:219], v96 offset:36928
	v_mfma_f32_32x32x16_bf16 v[16:31], v[224:227], v[220:223], v[16:31]
	ds_read_b128 v[224:227], v176 offset:64
	ds_read_b128 v[220:223], v176 offset:4672
	s_waitcnt lgkmcnt(5)
	v_mfma_f32_32x32x16_bf16 v[32:47], v[228:231], v[244:247], v[32:47]
	s_waitcnt lgkmcnt(4)
	v_mfma_f32_32x32x16_bf16 v[0:15], v[228:231], v[252:255], v[0:15]
	ds_read_b128 v[228:231], v96 offset:41536
	s_waitcnt lgkmcnt(4)
	v_mfma_f32_32x32x16_bf16 v[48:63], v[212:215], v[244:247], v[48:63]
	ds_read_b128 v[244:247], v96 offset:36960
	v_mfma_f32_32x32x16_bf16 v[16:31], v[212:215], v[252:255], v[16:31]
	ds_read_b128 v[212:215], v176 offset:96
	ds_read_b128 v[252:255], v176 offset:4704
	s_waitcnt lgkmcnt(5)
	v_mfma_f32_32x32x16_bf16 v[32:47], v[216:219], v[224:227], v[32:47]
	s_waitcnt vmcnt(15)
	ds_write_b128 v175, v[68:71] offset:18432
	global_load_dwordx4 v[68:71], v[152:153], off offset:1408
	s_waitcnt lgkmcnt(5)
	v_mfma_f32_32x32x16_bf16 v[0:15], v[216:219], v[220:223], v[0:15]
	ds_read_b128 v[216:219], v96 offset:41568
	s_waitcnt vmcnt(15)
	ds_write_b128 v175, v[84:87] offset:23040
	global_load_dwordx4 v[84:87], v[154:155], off offset:1408
	s_waitcnt lgkmcnt(6)
	v_mfma_f32_32x32x16_bf16 v[48:63], v[228:231], v[224:227], v[48:63]
	s_waitcnt vmcnt(15)
	ds_write_b128 v175, v[88:91] offset:27648
	global_load_dwordx4 v[88:91], v[156:157], off offset:1408
	v_mfma_f32_32x32x16_bf16 v[16:31], v[228:231], v[220:223], v[16:31]
	s_waitcnt vmcnt(15)
	ds_write_b128 v175, v[92:95] offset:32256
	global_load_dwordx4 v[92:95], v[158:159], off offset:1408
	s_waitcnt lgkmcnt(6)
	v_mfma_f32_32x32x16_bf16 v[32:47], v[244:247], v[212:215], v[32:47]
	s_waitcnt vmcnt(15)
	ds_write_b128 v175, v[98:101] offset:55296
	global_load_dwordx4 v[98:101], v[150:151], off offset:1408
	s_waitcnt lgkmcnt(6)
	v_mfma_f32_32x32x16_bf16 v[0:15], v[244:247], v[252:255], v[0:15]
	s_waitcnt vmcnt(15)
	ds_write_b128 v175, v[106:109] offset:59904
	global_load_dwordx4 v[106:109], v[160:161], off offset:1408
	s_waitcnt lgkmcnt(5)
	v_mfma_f32_32x32x16_bf16 v[48:63], v[216:219], v[212:215], v[48:63]
	s_waitcnt vmcnt(15)
	ds_write_b128 v175, v[110:113] offset:64512
	global_load_dwordx4 v[110:113], v[170:171], off offset:1408
	v_mfma_f32_32x32x16_bf16 v[16:31], v[216:219], v[252:255], v[16:31]
	s_waitcnt vmcnt(15)
	ds_write_b128 v177, v[114:117] offset:13824
	global_load_dwordx4 v[130:133], v[172:173], off offset:1408
	s_setprio 0
	s_waitcnt lgkmcnt(0)
	s_barrier
	s_setprio 1
	ds_read_b128 v[212:215], v96 offset:55296
	ds_read_b128 v[216:219], v176 offset:18432
	ds_read_b128 v[220:223], v176 offset:23040
	ds_read_b128 v[224:227], v96 offset:59904
	ds_read_b128 v[228:231], v96 offset:55328
	ds_read_b128 v[244:247], v176 offset:18464
	ds_read_b128 v[252:255], v176 offset:23072
	s_waitcnt lgkmcnt(5)
	v_mfma_f32_32x32x16_bf16 v[32:47], v[212:215], v[216:219], v[32:47]
	s_waitcnt lgkmcnt(4)
	v_mfma_f32_32x32x16_bf16 v[0:15], v[212:215], v[220:223], v[0:15]
	ds_read_b128 v[212:215], v96 offset:59936
	s_waitcnt lgkmcnt(4)
	v_mfma_f32_32x32x16_bf16 v[48:63], v[224:227], v[216:219], v[48:63]
	ds_read_b128 v[216:219], v96 offset:55360
	v_mfma_f32_32x32x16_bf16 v[16:31], v[224:227], v[220:223], v[16:31]
	ds_read_b128 v[224:227], v176 offset:18496
	ds_read_b128 v[220:223], v176 offset:23104
	s_waitcnt lgkmcnt(5)
	v_mfma_f32_32x32x16_bf16 v[32:47], v[228:231], v[244:247], v[32:47]
	s_waitcnt lgkmcnt(4)
	v_mfma_f32_32x32x16_bf16 v[0:15], v[228:231], v[252:255], v[0:15]
	ds_read_b128 v[228:231], v96 offset:59968
	s_waitcnt lgkmcnt(4)
	v_mfma_f32_32x32x16_bf16 v[48:63], v[212:215], v[244:247], v[48:63]
	ds_read_b128 v[244:247], v96 offset:55392
	v_mfma_f32_32x32x16_bf16 v[16:31], v[212:215], v[252:255], v[16:31]
	ds_read_b128 v[212:215], v176 offset:18528
	ds_read_b128 v[252:255], v176 offset:23136
	s_waitcnt lgkmcnt(5)
	v_mfma_f32_32x32x16_bf16 v[32:47], v[216:219], v[224:227], v[32:47]
	s_waitcnt vmcnt(15)
	ds_write_b128 v175, v[64:67]
	global_load_dwordx4 v[64:67], v[152:153], off offset:1536
	s_waitcnt lgkmcnt(5)
	v_mfma_f32_32x32x16_bf16 v[0:15], v[216:219], v[220:223], v[0:15]
	ds_read_b128 v[216:219], v96 offset:60000
	s_waitcnt vmcnt(15)
	ds_write_b128 v175, v[72:75] offset:4608
	global_load_dwordx4 v[72:75], v[154:155], off offset:1536
	s_waitcnt lgkmcnt(6)
	v_mfma_f32_32x32x16_bf16 v[48:63], v[228:231], v[224:227], v[48:63]
	s_waitcnt vmcnt(15)
	ds_write_b128 v175, v[76:79] offset:9216
	global_load_dwordx4 v[76:79], v[156:157], off offset:1536
	v_mfma_f32_32x32x16_bf16 v[16:31], v[228:231], v[220:223], v[16:31]
	s_waitcnt vmcnt(15)
	ds_write_b128 v175, v[80:83] offset:13824
	global_load_dwordx4 v[80:83], v[158:159], off offset:1536
	s_waitcnt lgkmcnt(6)
	v_mfma_f32_32x32x16_bf16 v[32:47], v[244:247], v[212:215], v[32:47]
	s_waitcnt vmcnt(15)
	ds_write_b128 v175, v[102:105] offset:36864
	global_load_dwordx4 v[114:117], v[150:151], off offset:1536
	s_waitcnt lgkmcnt(6)
	v_mfma_f32_32x32x16_bf16 v[0:15], v[244:247], v[252:255], v[0:15]
	s_waitcnt vmcnt(15)
	ds_write_b128 v175, v[118:121] offset:41472
	s_waitcnt vmcnt(14)
	ds_write_b128 v175, v[122:125] offset:46080
	s_waitcnt lgkmcnt(6)
	v_mfma_f32_32x32x16_bf16 v[48:63], v[216:219], v[212:215], v[48:63]
	global_load_dwordx4 v[122:125], v[160:161], off offset:1536
	s_waitcnt vmcnt(14)
	ds_write_b128 v175, v[126:129] offset:50688
	v_mfma_f32_32x32x16_bf16 v[16:31], v[216:219], v[252:255], v[16:31]
	global_load_dwordx4 v[126:129], v[170:171], off offset:1536
	global_load_dwordx4 v[134:137], v[172:173], off offset:1536
	s_setprio 0
	s_waitcnt lgkmcnt(0)
	s_barrier
	s_setprio 1
	ds_read_b128 v[212:215], v96 offset:36864
	ds_read_b128 v[216:219], v176
	ds_read_b128 v[220:223], v176 offset:4608
	ds_read_b128 v[224:227], v96 offset:41472
	ds_read_b128 v[228:231], v96 offset:36896
	ds_read_b128 v[244:247], v176 offset:32
	ds_read_b128 v[252:255], v176 offset:4640
	s_waitcnt lgkmcnt(5)
	v_mfma_f32_32x32x16_bf16 v[32:47], v[212:215], v[216:219], v[32:47]
	s_waitcnt lgkmcnt(4)
	v_mfma_f32_32x32x16_bf16 v[0:15], v[212:215], v[220:223], v[0:15]
	ds_read_b128 v[212:215], v96 offset:41504
	s_waitcnt lgkmcnt(4)
	v_mfma_f32_32x32x16_bf16 v[48:63], v[224:227], v[216:219], v[48:63]
	ds_read_b128 v[216:219], v96 offset:36928
	v_mfma_f32_32x32x16_bf16 v[16:31], v[224:227], v[220:223], v[16:31]
	ds_read_b128 v[224:227], v176 offset:64
	ds_read_b128 v[220:223], v176 offset:4672
	s_waitcnt lgkmcnt(5)
	v_mfma_f32_32x32x16_bf16 v[32:47], v[228:231], v[244:247], v[32:47]
	s_waitcnt lgkmcnt(4)
	v_mfma_f32_32x32x16_bf16 v[0:15], v[228:231], v[252:255], v[0:15]
	ds_read_b128 v[228:231], v96 offset:41536
	s_waitcnt lgkmcnt(4)
	v_mfma_f32_32x32x16_bf16 v[48:63], v[212:215], v[244:247], v[48:63]
	ds_read_b128 v[244:247], v96 offset:36960
	v_mfma_f32_32x32x16_bf16 v[16:31], v[212:215], v[252:255], v[16:31]
	ds_read_b128 v[212:215], v176 offset:96
	ds_read_b128 v[252:255], v176 offset:4704
	s_waitcnt lgkmcnt(5)
	v_mfma_f32_32x32x16_bf16 v[32:47], v[216:219], v[224:227], v[32:47]
	s_waitcnt vmcnt(15)
	ds_write_b128 v175, v[68:71] offset:18432
	s_waitcnt vmcnt(14)
	ds_write_b128 v175, v[84:87] offset:23040
	s_waitcnt lgkmcnt(6)
	v_mfma_f32_32x32x16_bf16 v[0:15], v[216:219], v[220:223], v[0:15]
	ds_read_b128 v[216:219], v96 offset:41568
	s_waitcnt vmcnt(13)
	ds_write_b128 v175, v[88:91] offset:27648
	s_waitcnt vmcnt(12)
	ds_write_b128 v175, v[92:95] offset:32256
	s_waitcnt lgkmcnt(8)
	v_mfma_f32_32x32x16_bf16 v[48:63], v[228:231], v[224:227], v[48:63]
	s_waitcnt vmcnt(11)
	ds_write_b128 v175, v[98:101] offset:55296
	v_mfma_f32_32x32x16_bf16 v[16:31], v[228:231], v[220:223], v[16:31]
	global_load_dwordx4 v[98:101], v[152:153], off offset:1664
	global_load_dwordx4 v[102:105], v[154:155], off offset:1664
	s_waitcnt vmcnt(12)
	ds_write_b128 v175, v[106:109] offset:59904
	s_waitcnt lgkmcnt(8)
	v_mfma_f32_32x32x16_bf16 v[32:47], v[244:247], v[212:215], v[32:47]
	global_load_dwordx4 v[106:109], v[156:157], off offset:1664
	s_waitcnt vmcnt(12)
	ds_write_b128 v175, v[110:113] offset:64512
	s_waitcnt lgkmcnt(8)
	v_mfma_f32_32x32x16_bf16 v[0:15], v[244:247], v[252:255], v[0:15]
	global_load_dwordx4 v[110:113], v[158:159], off offset:1664
	global_load_dwordx4 v[118:121], v[150:151], off offset:1664
	s_waitcnt lgkmcnt(5)
	v_mfma_f32_32x32x16_bf16 v[48:63], v[216:219], v[212:215], v[48:63]
	s_waitcnt vmcnt(13)
	ds_write_b128 v177, v[130:133] offset:13824
	global_load_dwordx4 v[130:133], v[160:161], off offset:1664
	v_mfma_f32_32x32x16_bf16 v[16:31], v[216:219], v[252:255], v[16:31]
	global_load_dwordx4 v[138:141], v[170:171], off offset:1664
	global_load_dwordx4 v[142:145], v[172:173], off offset:1664
	s_setprio 0
	s_waitcnt lgkmcnt(0)
	s_barrier
	s_setprio 1
	ds_read_b128 v[212:215], v96 offset:55296
	ds_read_b128 v[216:219], v176 offset:18432
	ds_read_b128 v[220:223], v176 offset:23040
	ds_read_b128 v[224:227], v96 offset:59904
	ds_read_b128 v[228:231], v96 offset:55328
	ds_read_b128 v[244:247], v176 offset:18464
	ds_read_b128 v[252:255], v176 offset:23072
	s_waitcnt lgkmcnt(5)
	v_mfma_f32_32x32x16_bf16 v[32:47], v[212:215], v[216:219], v[32:47]
	s_waitcnt lgkmcnt(4)
	v_mfma_f32_32x32x16_bf16 v[0:15], v[212:215], v[220:223], v[0:15]
	ds_read_b128 v[212:215], v96 offset:59936
	s_waitcnt lgkmcnt(4)
	v_mfma_f32_32x32x16_bf16 v[48:63], v[224:227], v[216:219], v[48:63]
	ds_read_b128 v[216:219], v96 offset:55360
	v_mfma_f32_32x32x16_bf16 v[16:31], v[224:227], v[220:223], v[16:31]
	ds_read_b128 v[224:227], v176 offset:18496
	ds_read_b128 v[220:223], v176 offset:23104
	s_waitcnt lgkmcnt(5)
	v_mfma_f32_32x32x16_bf16 v[32:47], v[228:231], v[244:247], v[32:47]
	s_waitcnt lgkmcnt(4)
	v_mfma_f32_32x32x16_bf16 v[0:15], v[228:231], v[252:255], v[0:15]
	ds_read_b128 v[228:231], v96 offset:59968
	s_waitcnt lgkmcnt(4)
	v_mfma_f32_32x32x16_bf16 v[48:63], v[212:215], v[244:247], v[48:63]
	ds_read_b128 v[244:247], v96 offset:55392
	v_mfma_f32_32x32x16_bf16 v[16:31], v[212:215], v[252:255], v[16:31]
	ds_read_b128 v[212:215], v176 offset:18528
	ds_read_b128 v[252:255], v176 offset:23136
	s_waitcnt lgkmcnt(5)
	v_mfma_f32_32x32x16_bf16 v[32:47], v[216:219], v[224:227], v[32:47]
	s_waitcnt vmcnt(15)
	ds_write_b128 v175, v[64:67]
	global_load_dwordx4 v[64:67], v[152:153], off offset:1792
	s_waitcnt lgkmcnt(5)
	v_mfma_f32_32x32x16_bf16 v[0:15], v[216:219], v[220:223], v[0:15]
	ds_read_b128 v[216:219], v96 offset:60000
	s_waitcnt vmcnt(15)
	ds_write_b128 v175, v[72:75] offset:4608
	global_load_dwordx4 v[68:71], v[154:155], off offset:1792
	s_waitcnt lgkmcnt(6)
	v_mfma_f32_32x32x16_bf16 v[48:63], v[228:231], v[224:227], v[48:63]
	s_waitcnt vmcnt(15)
	ds_write_b128 v175, v[76:79] offset:9216
	global_load_dwordx4 v[72:75], v[156:157], off offset:1792
	v_mfma_f32_32x32x16_bf16 v[16:31], v[228:231], v[220:223], v[16:31]
	s_waitcnt vmcnt(15)
	ds_write_b128 v175, v[80:83] offset:13824
	global_load_dwordx4 v[76:79], v[158:159], off offset:1792
	s_waitcnt lgkmcnt(6)
	v_mfma_f32_32x32x16_bf16 v[32:47], v[244:247], v[212:215], v[32:47]
	s_waitcnt vmcnt(15)
	ds_write_b128 v175, v[114:117] offset:36864
	global_load_dwordx4 v[80:83], v[150:151], off offset:1792
	s_waitcnt lgkmcnt(6)
	v_mfma_f32_32x32x16_bf16 v[0:15], v[244:247], v[252:255], v[0:15]
	s_waitcnt vmcnt(15)
	ds_write_b128 v175, v[122:125] offset:41472
	global_load_dwordx4 v[84:87], v[160:161], off offset:1792
	s_waitcnt lgkmcnt(5)
	v_mfma_f32_32x32x16_bf16 v[48:63], v[216:219], v[212:215], v[48:63]
	s_waitcnt vmcnt(15)
	ds_write_b128 v175, v[126:129] offset:46080
	global_load_dwordx4 v[88:91], v[170:171], off offset:1792
	v_mfma_f32_32x32x16_bf16 v[16:31], v[216:219], v[252:255], v[16:31]
	s_waitcnt vmcnt(15)
	ds_write_b128 v175, v[134:137] offset:50688
	global_load_dwordx4 v[92:95], v[172:173], off offset:1792
	s_setprio 0
	s_waitcnt lgkmcnt(0)
	s_barrier
	s_setprio 1
	ds_read_b128 v[212:215], v96 offset:36864
	ds_read_b128 v[216:219], v176
	ds_read_b128 v[220:223], v176 offset:4608
	ds_read_b128 v[224:227], v96 offset:41472
	ds_read_b128 v[228:231], v96 offset:36896
	ds_read_b128 v[244:247], v176 offset:32
	ds_read_b128 v[252:255], v176 offset:4640
	s_waitcnt lgkmcnt(5)
	v_mfma_f32_32x32x16_bf16 v[32:47], v[212:215], v[216:219], v[32:47]
	s_waitcnt lgkmcnt(4)
	v_mfma_f32_32x32x16_bf16 v[0:15], v[212:215], v[220:223], v[0:15]
	ds_read_b128 v[212:215], v96 offset:41504
	s_waitcnt lgkmcnt(4)
	v_mfma_f32_32x32x16_bf16 v[48:63], v[224:227], v[216:219], v[48:63]
	ds_read_b128 v[216:219], v96 offset:36928
	v_mfma_f32_32x32x16_bf16 v[16:31], v[224:227], v[220:223], v[16:31]
	ds_read_b128 v[224:227], v176 offset:64
	ds_read_b128 v[220:223], v176 offset:4672
	s_waitcnt lgkmcnt(5)
	v_mfma_f32_32x32x16_bf16 v[32:47], v[228:231], v[244:247], v[32:47]
	s_waitcnt lgkmcnt(4)
	v_mfma_f32_32x32x16_bf16 v[0:15], v[228:231], v[252:255], v[0:15]
	ds_read_b128 v[228:231], v96 offset:41536
	s_waitcnt lgkmcnt(4)
	v_mfma_f32_32x32x16_bf16 v[48:63], v[212:215], v[244:247], v[48:63]
	ds_read_b128 v[244:247], v96 offset:36960
	v_mfma_f32_32x32x16_bf16 v[16:31], v[212:215], v[252:255], v[16:31]
	ds_read_b128 v[212:215], v176 offset:96
	ds_read_b128 v[252:255], v176 offset:4704
	s_waitcnt lgkmcnt(5)
	v_mfma_f32_32x32x16_bf16 v[32:47], v[216:219], v[224:227], v[32:47]
	s_waitcnt vmcnt(15)
	ds_write_b128 v175, v[98:101] offset:18432
	s_waitcnt vmcnt(14)
	ds_write_b128 v175, v[102:105] offset:23040
	s_waitcnt lgkmcnt(6)
	v_mfma_f32_32x32x16_bf16 v[0:15], v[216:219], v[220:223], v[0:15]
	ds_read_b128 v[216:219], v96 offset:41568
	global_load_dwordx4 v[100:103], v[152:153], off offset:1920
	s_waitcnt vmcnt(14)
	ds_write_b128 v175, v[106:109] offset:27648
	s_waitcnt lgkmcnt(7)
	v_mfma_f32_32x32x16_bf16 v[48:63], v[228:231], v[224:227], v[48:63]
	global_load_dwordx4 v[104:107], v[154:155], off offset:1920
	s_waitcnt vmcnt(14)
	ds_write_b128 v175, v[110:113] offset:32256
	v_mfma_f32_32x32x16_bf16 v[16:31], v[228:231], v[220:223], v[16:31]
	global_load_dwordx4 v[108:111], v[156:157], off offset:1920
	global_load_dwordx4 v[112:115], v[158:159], off offset:1920
	s_waitcnt lgkmcnt(6)
	v_mfma_f32_32x32x16_bf16 v[32:47], v[244:247], v[212:215], v[32:47]
	s_waitcnt vmcnt(15)
	ds_write_b128 v175, v[118:121] offset:55296
	global_load_dwordx4 v[116:119], v[150:151], off offset:1920
	s_waitcnt lgkmcnt(6)
	v_mfma_f32_32x32x16_bf16 v[0:15], v[244:247], v[252:255], v[0:15]
	s_waitcnt vmcnt(15)
	ds_write_b128 v175, v[130:133] offset:59904
	global_load_dwordx4 v[124:127], v[160:161], off offset:1920
	s_waitcnt lgkmcnt(4)
	v_mfma_f32_32x32x16_bf16 v[48:63], v[216:219], v[212:215], v[48:63]
	s_waitcnt vmcnt(15)
	ds_write_b128 v175, v[138:141] offset:64512
	global_load_dwordx4 v[120:123], v[170:171], off offset:1920
	v_mfma_f32_32x32x16_bf16 v[16:31], v[216:219], v[252:255], v[16:31]
	s_waitcnt vmcnt(15)
	ds_write_b128 v177, v[142:145] offset:13824
	global_load_dwordx4 v[128:131], v[172:173], off offset:1920
	s_setprio 0
	s_waitcnt lgkmcnt(0)
	s_barrier
	s_setprio 1
	ds_read_b128 v[212:215], v96 offset:55296
	ds_read_b128 v[216:219], v176 offset:18432
	ds_read_b128 v[220:223], v176 offset:23040
	ds_read_b128 v[224:227], v96 offset:59904
	ds_read_b128 v[228:231], v96 offset:55328
	ds_read_b128 v[244:247], v176 offset:18464
	ds_read_b128 v[252:255], v176 offset:23072
	s_waitcnt lgkmcnt(5)
	v_mfma_f32_32x32x16_bf16 v[32:47], v[212:215], v[216:219], v[32:47]
	s_waitcnt lgkmcnt(4)
	v_mfma_f32_32x32x16_bf16 v[0:15], v[212:215], v[220:223], v[0:15]
	ds_read_b128 v[212:215], v96 offset:59936
	s_waitcnt lgkmcnt(4)
	v_mfma_f32_32x32x16_bf16 v[48:63], v[224:227], v[216:219], v[48:63]
	ds_read_b128 v[216:219], v96 offset:55360
	v_mfma_f32_32x32x16_bf16 v[16:31], v[224:227], v[220:223], v[16:31]
	ds_read_b128 v[224:227], v176 offset:18496
	ds_read_b128 v[220:223], v176 offset:23104
	s_waitcnt lgkmcnt(5)
	v_mfma_f32_32x32x16_bf16 v[32:47], v[228:231], v[244:247], v[32:47]
	s_waitcnt lgkmcnt(4)
	v_mfma_f32_32x32x16_bf16 v[0:15], v[228:231], v[252:255], v[0:15]
	ds_read_b128 v[228:231], v96 offset:59968
	s_waitcnt lgkmcnt(4)
	v_mfma_f32_32x32x16_bf16 v[48:63], v[212:215], v[244:247], v[48:63]
	ds_read_b128 v[244:247], v96 offset:55392
	v_mfma_f32_32x32x16_bf16 v[16:31], v[212:215], v[252:255], v[16:31]
	ds_read_b128 v[212:215], v176 offset:18528
	ds_read_b128 v[252:255], v176 offset:23136
	s_waitcnt lgkmcnt(5)
	v_mfma_f32_32x32x16_bf16 v[32:47], v[216:219], v[224:227], v[32:47]
	s_waitcnt lgkmcnt(4)
	v_mfma_f32_32x32x16_bf16 v[0:15], v[216:219], v[220:223], v[0:15]
	ds_read_b128 v[216:219], v96 offset:60000
	s_waitcnt lgkmcnt(4)
	v_mfma_f32_32x32x16_bf16 v[48:63], v[228:231], v[224:227], v[48:63]
	v_mfma_f32_32x32x16_bf16 v[16:31], v[228:231], v[220:223], v[16:31]
	s_waitcnt lgkmcnt(2)
	v_mfma_f32_32x32x16_bf16 v[32:47], v[244:247], v[212:215], v[32:47]
	s_waitcnt lgkmcnt(1)
	v_mfma_f32_32x32x16_bf16 v[0:15], v[244:247], v[252:255], v[0:15]
	s_waitcnt lgkmcnt(0)
	v_mfma_f32_32x32x16_bf16 v[48:63], v[216:219], v[212:215], v[48:63]
	v_mfma_f32_32x32x16_bf16 v[16:31], v[216:219], v[252:255], v[16:31]
	s_setprio 0
	v_cndmask_b32_e64 v98, 0, 1, s[12:13]
	v_cmp_ne_u32_e64 s[40:41], 1, v98
	s_andn2_b64 vcc, exec, s[12:13]
	s_waitcnt vmcnt(15)
	ds_write_b128 v175, v[64:67]
	s_waitcnt vmcnt(14)
	ds_write_b128 v175, v[68:71] offset:4608
	s_waitcnt vmcnt(13)
	ds_write_b128 v175, v[72:75] offset:9216
	s_waitcnt vmcnt(12)
	ds_write_b128 v175, v[76:79] offset:13824
	s_waitcnt vmcnt(11)
	ds_write_b128 v175, v[80:83] offset:36864
	s_waitcnt vmcnt(10)
	ds_write_b128 v175, v[84:87] offset:41472
	s_waitcnt vmcnt(9)
	ds_write_b128 v175, v[88:91] offset:46080
	s_waitcnt vmcnt(8)
	ds_write_b128 v175, v[92:95] offset:50688
	s_cbranch_vccnz .LBB0_270
	v_add_co_u32_e32 v68, vcc, 0x10000, v148
	global_load_dwordx4 v[64:67], v[148:149], off
	s_nop 0
	v_addc_co_u32_e32 v69, vcc, 0, v149, vcc
	v_add_co_u32_e32 v72, vcc, 0x20000, v148
	s_nop 1
	v_addc_co_u32_e32 v73, vcc, 0, v149, vcc
	v_add_co_u32_e32 v76, vcc, 0x30000, v148
	global_load_dwordx4 v[68:71], v[68:69], off
	global_load_dwordx4 v[72:75], v[72:73], off
	v_addc_co_u32_e32 v77, vcc, 0, v149, vcc
	v_add_co_u32_e32 v84, vcc, 0x10000, v146
	global_load_dwordx4 v[76:79], v[76:77], off
	s_nop 0
	global_load_dwordx4 v[80:83], v[146:147], off
	v_addc_co_u32_e32 v85, vcc, 0, v147, vcc
	v_add_co_u32_e32 v88, vcc, 0x20000, v146
	s_nop 1
	v_addc_co_u32_e32 v89, vcc, 0, v147, vcc
	v_add_co_u32_e32 v92, vcc, 0x30000, v146
	global_load_dwordx4 v[84:87], v[84:85], off
	s_nop 0
	global_load_dwordx4 v[88:91], v[88:89], off
	v_addc_co_u32_e32 v93, vcc, 0, v147, vcc
	global_load_dwordx4 v[92:95], v[92:93], off
.LBB0_270:
	s_waitcnt lgkmcnt(0)
	s_barrier
	s_setprio 1
	ds_read_b128 v[212:215], v96 offset:36864
	ds_read_b128 v[216:219], v176
	ds_read_b128 v[220:223], v176 offset:4608
	ds_read_b128 v[224:227], v96 offset:41472
	ds_read_b128 v[228:231], v96 offset:36896
	ds_read_b128 v[244:247], v176 offset:32
	ds_read_b128 v[252:255], v176 offset:4640
	s_waitcnt lgkmcnt(5)
	v_mfma_f32_32x32x16_bf16 v[32:47], v[212:215], v[216:219], v[32:47]
	s_waitcnt lgkmcnt(4)
	v_mfma_f32_32x32x16_bf16 v[0:15], v[212:215], v[220:223], v[0:15]
	ds_read_b128 v[212:215], v96 offset:41504
	s_waitcnt lgkmcnt(4)
	v_mfma_f32_32x32x16_bf16 v[48:63], v[224:227], v[216:219], v[48:63]
	ds_read_b128 v[216:219], v96 offset:36928
	v_mfma_f32_32x32x16_bf16 v[16:31], v[224:227], v[220:223], v[16:31]
	ds_read_b128 v[224:227], v176 offset:64
	ds_read_b128 v[220:223], v176 offset:4672
	s_waitcnt lgkmcnt(5)
	v_mfma_f32_32x32x16_bf16 v[32:47], v[228:231], v[244:247], v[32:47]
	s_waitcnt lgkmcnt(4)
	v_mfma_f32_32x32x16_bf16 v[0:15], v[228:231], v[252:255], v[0:15]
	ds_read_b128 v[228:231], v96 offset:41536
	s_waitcnt lgkmcnt(4)
	v_mfma_f32_32x32x16_bf16 v[48:63], v[212:215], v[244:247], v[48:63]
	ds_read_b128 v[244:247], v96 offset:36960
	v_mfma_f32_32x32x16_bf16 v[16:31], v[212:215], v[252:255], v[16:31]
	ds_read_b128 v[212:215], v176 offset:96
	ds_read_b128 v[252:255], v176 offset:4704
	s_waitcnt lgkmcnt(5)
	v_mfma_f32_32x32x16_bf16 v[32:47], v[216:219], v[224:227], v[32:47]
	s_waitcnt lgkmcnt(4)
	v_mfma_f32_32x32x16_bf16 v[0:15], v[216:219], v[220:223], v[0:15]
	ds_read_b128 v[216:219], v96 offset:41568
	s_waitcnt lgkmcnt(4)
	v_mfma_f32_32x32x16_bf16 v[48:63], v[228:231], v[224:227], v[48:63]
	v_mfma_f32_32x32x16_bf16 v[16:31], v[228:231], v[220:223], v[16:31]
	s_waitcnt lgkmcnt(2)
	v_mfma_f32_32x32x16_bf16 v[32:47], v[244:247], v[212:215], v[32:47]
	s_waitcnt lgkmcnt(1)
	v_mfma_f32_32x32x16_bf16 v[0:15], v[244:247], v[252:255], v[0:15]
	s_waitcnt lgkmcnt(0)
	v_mfma_f32_32x32x16_bf16 v[48:63], v[216:219], v[212:215], v[48:63]
	v_mfma_f32_32x32x16_bf16 v[16:31], v[216:219], v[252:255], v[16:31]
	s_setprio 0
	s_and_b64 vcc, exec, s[40:41]
	s_waitcnt vmcnt(7)
	ds_write_b128 v175, v[100:103] offset:18432
	s_waitcnt vmcnt(6)
	ds_write_b128 v175, v[104:107] offset:23040
	s_waitcnt vmcnt(5)
	ds_write_b128 v175, v[108:111] offset:27648
	s_waitcnt vmcnt(4)
	ds_write_b128 v175, v[112:115] offset:32256
	s_waitcnt vmcnt(3)
	ds_write_b128 v175, v[116:119] offset:55296
	s_waitcnt vmcnt(2)
	ds_write_b128 v175, v[124:127] offset:59904
	s_waitcnt vmcnt(1)
	ds_write_b128 v175, v[120:123] offset:64512
	s_waitcnt vmcnt(0)
	ds_write_b128 v177, v[128:131] offset:13824
	s_cbranch_vccnz .LBB0_272
	v_add_co_u32_e32 v98, vcc, 0x10000, v148
	global_load_dwordx4 v[100:103], v[148:149], off offset:128
	s_nop 0
	v_addc_co_u32_e32 v99, vcc, 0, v149, vcc
	v_add_co_u32_e32 v108, vcc, 0x20000, v148
	s_nop 1
	v_addc_co_u32_e32 v109, vcc, 0, v149, vcc
	global_load_dwordx4 v[104:107], v[98:99], off offset:128
	global_load_dwordx4 v[108:111], v[108:109], off offset:128
	v_add_co_u32_e32 v98, vcc, 0x30000, v148
	s_nop 1
	v_addc_co_u32_e32 v99, vcc, 0, v149, vcc
	global_load_dwordx4 v[112:115], v[98:99], off offset:128
	global_load_dwordx4 v[116:119], v[146:147], off offset:128
	v_add_co_u32_e32 v98, vcc, 0x10000, v146
	s_nop 1
	v_addc_co_u32_e32 v99, vcc, 0, v147, vcc
	v_add_co_u32_e32 v120, vcc, 0x20000, v146
	s_nop 1
	v_addc_co_u32_e32 v121, vcc, 0, v147, vcc
	global_load_dwordx4 v[124:127], v[98:99], off offset:128
	s_nop 0
	global_load_dwordx4 v[120:123], v[120:121], off offset:128
	v_add_co_u32_e32 v98, vcc, 0x30000, v146
	s_nop 1
	v_addc_co_u32_e32 v99, vcc, 0, v147, vcc
	global_load_dwordx4 v[128:131], v[98:99], off offset:128
.LBB0_272:
	s_waitcnt lgkmcnt(0)
	s_barrier
	s_setprio 1
	ds_read_b128 v[212:215], v96 offset:55296
	ds_read_b128 v[216:219], v176 offset:18432
	ds_read_b128 v[220:223], v176 offset:23040
	ds_read_b128 v[224:227], v96 offset:59904
	ds_read_b128 v[228:231], v96 offset:55328
	ds_read_b128 v[244:247], v176 offset:18464
	ds_read_b128 v[252:255], v176 offset:23072
	s_waitcnt lgkmcnt(5)
	v_mfma_f32_32x32x16_bf16 v[32:47], v[212:215], v[216:219], v[32:47]
	s_waitcnt lgkmcnt(4)
	v_mfma_f32_32x32x16_bf16 v[0:15], v[212:215], v[220:223], v[0:15]
	ds_read_b128 v[212:215], v96 offset:59936
	s_waitcnt lgkmcnt(4)
	v_mfma_f32_32x32x16_bf16 v[48:63], v[224:227], v[216:219], v[48:63]
	ds_read_b128 v[216:219], v96 offset:55360
	v_mfma_f32_32x32x16_bf16 v[16:31], v[224:227], v[220:223], v[16:31]
	ds_read_b128 v[224:227], v176 offset:18496
	ds_read_b128 v[220:223], v176 offset:23104
	s_waitcnt lgkmcnt(5)
	v_mfma_f32_32x32x16_bf16 v[32:47], v[228:231], v[244:247], v[32:47]
	s_waitcnt lgkmcnt(4)
	v_mfma_f32_32x32x16_bf16 v[0:15], v[228:231], v[252:255], v[0:15]
	ds_read_b128 v[228:231], v96 offset:59968
	s_waitcnt lgkmcnt(4)
	v_mfma_f32_32x32x16_bf16 v[48:63], v[212:215], v[244:247], v[48:63]
	ds_read_b128 v[244:247], v96 offset:55392
	v_mfma_f32_32x32x16_bf16 v[16:31], v[212:215], v[252:255], v[16:31]
	ds_read_b128 v[212:215], v176 offset:18528
	ds_read_b128 v[252:255], v176 offset:23136
	s_waitcnt lgkmcnt(5)
	v_mfma_f32_32x32x16_bf16 v[32:47], v[216:219], v[224:227], v[32:47]
	s_waitcnt lgkmcnt(4)
	v_mfma_f32_32x32x16_bf16 v[0:15], v[216:219], v[220:223], v[0:15]
	ds_read_b128 v[216:219], v96 offset:60000
	s_waitcnt lgkmcnt(4)
	v_mfma_f32_32x32x16_bf16 v[48:63], v[228:231], v[224:227], v[48:63]
	v_mfma_f32_32x32x16_bf16 v[16:31], v[228:231], v[220:223], v[16:31]
	s_waitcnt lgkmcnt(2)
	v_mfma_f32_32x32x16_bf16 v[32:47], v[244:247], v[212:215], v[32:47]
	s_waitcnt lgkmcnt(1)
	v_mfma_f32_32x32x16_bf16 v[0:15], v[244:247], v[252:255], v[0:15]
	s_waitcnt lgkmcnt(0)
	v_mfma_f32_32x32x16_bf16 v[48:63], v[216:219], v[212:215], v[48:63]
	v_mfma_f32_32x32x16_bf16 v[16:31], v[216:219], v[252:255], v[16:31]
	s_setprio 0
	s_and_b64 vcc, exec, s[40:41]
	s_cbranch_vccnz .LBB0_263
	ds_write_b128 v175, v[64:67]
	ds_write_b128 v175, v[68:71] offset:4608
	ds_write_b128 v175, v[72:75] offset:9216
	ds_write_b128 v175, v[76:79] offset:13824
	ds_write_b128 v175, v[80:83] offset:36864
	ds_write_b128 v175, v[84:87] offset:41472
	ds_write_b128 v175, v[88:91] offset:46080
	ds_write_b128 v175, v[92:95] offset:50688
	v_add_co_u32_e32 v68, vcc, 0x10000, v148
	global_load_dwordx4 v[64:67], v[148:149], off offset:256
	s_nop 0
	v_addc_co_u32_e32 v69, vcc, 0, v149, vcc
	v_add_co_u32_e32 v72, vcc, 0x20000, v148
	s_nop 1
	v_addc_co_u32_e32 v73, vcc, 0, v149, vcc
	v_add_co_u32_e32 v76, vcc, 0x30000, v148
	global_load_dwordx4 v[68:71], v[68:69], off offset:256
	s_nop 0
	global_load_dwordx4 v[72:75], v[72:73], off offset:256
	v_addc_co_u32_e32 v77, vcc, 0, v149, vcc
	v_add_co_u32_e32 v84, vcc, 0x10000, v146
	global_load_dwordx4 v[76:79], v[76:77], off offset:256
	global_load_dwordx4 v[80:83], v[146:147], off offset:256
	v_addc_co_u32_e32 v85, vcc, 0, v147, vcc
	v_add_co_u32_e32 v88, vcc, 0x20000, v146
	s_nop 1
	v_addc_co_u32_e32 v89, vcc, 0, v147, vcc
	v_add_co_u32_e32 v92, vcc, 0x30000, v146
	global_load_dwordx4 v[84:87], v[84:85], off offset:256
	global_load_dwordx4 v[88:91], v[88:89], off offset:256
	v_addc_co_u32_e32 v93, vcc, 0, v147, vcc
	global_load_dwordx4 v[92:95], v[92:93], off offset:256
	s_branch .LBB0_263

.LBB0_325:
	s_lshl_b32 s6, s41, 7
	s_min_i32 s2, s6, 0x4000
	s_ashr_i32 s2, s2, 11
	v_add_u32_e32 v136, s6, v169
	s_mul_hi_i32 s3, s2, 0x9000
	s_mul_i32 s2, s2, 0x9000
	v_lshl_or_b32 v98, s40, 7, v208
	v_ashrrev_i32_e32 v137, 31, v136
	s_add_u32 s2, s4, s2
	v_ashrrev_i32_e32 v99, 31, v98
	v_lshlrev_b64 v[132:133], 12, v[136:137]
	v_or_b32_e32 v136, 32, v136
	s_addc_u32 s3, s10, s3
	v_lshlrev_b64 v[98:99], 2, v[98:99]
	v_ashrrev_i32_e32 v137, 31, v136
	v_lshl_add_u64 v[134:135], s[2:3], 0, v[98:99]
	v_lshl_add_u64 v[98:99], s[92:93], 0, v[98:99]
	v_lshlrev_b64 v[136:137], 12, v[136:137]
	s_waitcnt lgkmcnt(0)
	s_barrier
	v_lshl_add_u64 v[132:133], v[98:99], 0, v[132:133]
	v_lshl_add_u64 v[98:99], v[98:99], 0, v[136:137]
	global_load_dwordx4 v[136:139], v[134:135], off
	global_load_dwordx4 v[140:143], v[132:133], off
	global_load_dwordx4 v[144:147], v[98:99], off
	s_mov_b64 s[38:39], 0
	s_and_b64 vcc, exec, s[0:1]
	s_mov_b32 s41, s11
	s_waitcnt vmcnt(2)
	v_pk_mul_f32 v[136:137], v[136:137], 0.5 op_sel_hi:[1,0]
	s_waitcnt vmcnt(1)
	v_pk_fma_f32 v[32:33], v[32:33], v[136:137], v[140:141]
	s_waitcnt vmcnt(0)
	v_pk_fma_f32 v[48:49], v[48:49], v[136:137], v[144:145]
	v_pk_mul_f32 v[136:137], v[138:139], 0.5 op_sel_hi:[1,0]
	v_pk_fma_f32 v[34:35], v[34:35], v[136:137], v[142:143]
	global_store_dwordx4 v[132:133], v[32:35], off
	v_pk_fma_f32 v[50:51], v[50:51], v[136:137], v[146:147]
	global_load_dwordx4 v[32:35], v[134:135], off offset:32
	global_load_dwordx4 v[136:139], v[98:99], off offset:32
	s_waitcnt vmcnt(1)
	v_pk_mul_f32 v[140:141], v[32:33], 0.5 op_sel_hi:[1,0]
	global_store_dwordx4 v[98:99], v[48:51], off
	global_load_dwordx4 v[48:51], v[132:133], off offset:32
	s_waitcnt vmcnt(0)
	v_pk_fma_f32 v[32:33], v[36:37], v[140:141], v[48:49]
	v_pk_mul_f32 v[48:49], v[34:35], 0.5 op_sel_hi:[1,0]
	v_pk_fma_f32 v[36:37], v[52:53], v[140:141], v[136:137]
	v_pk_fma_f32 v[34:35], v[38:39], v[48:49], v[50:51]
	global_store_dwordx4 v[132:133], v[32:35], off offset:32
	v_pk_fma_f32 v[38:39], v[54:55], v[48:49], v[138:139]
	global_load_dwordx4 v[32:35], v[134:135], off offset:64
	global_load_dwordx4 v[48:51], v[98:99], off offset:64
	s_waitcnt vmcnt(1)
	v_pk_mul_f32 v[52:53], v[32:33], 0.5 op_sel_hi:[1,0]
	global_store_dwordx4 v[98:99], v[36:39], off offset:32
	global_load_dwordx4 v[36:39], v[132:133], off offset:64
	s_waitcnt vmcnt(0)
	v_pk_fma_f32 v[32:33], v[40:41], v[52:53], v[36:37]
	v_pk_mul_f32 v[40:41], v[34:35], 0.5 op_sel_hi:[1,0]
	v_pk_fma_f32 v[36:37], v[56:57], v[52:53], v[48:49]
	v_pk_fma_f32 v[34:35], v[42:43], v[40:41], v[38:39]
	global_store_dwordx4 v[132:133], v[32:35], off offset:64
	v_pk_fma_f32 v[38:39], v[58:59], v[40:41], v[50:51]
	global_load_dwordx4 v[32:35], v[134:135], off offset:96
	global_load_dwordx4 v[40:43], v[98:99], off offset:96
	s_waitcnt vmcnt(1)
	v_pk_mul_f32 v[48:49], v[32:33], 0.5 op_sel_hi:[1,0]
	global_store_dwordx4 v[98:99], v[36:39], off offset:64
	global_load_dwordx4 v[36:39], v[132:133], off offset:96
	s_waitcnt vmcnt(0)
	v_pk_fma_f32 v[32:33], v[44:45], v[48:49], v[36:37]
	v_pk_fma_f32 v[36:37], v[60:61], v[48:49], v[40:41]
	v_pk_mul_f32 v[40:41], v[34:35], 0.5 op_sel_hi:[1,0]
	v_pk_fma_f32 v[34:35], v[46:47], v[40:41], v[38:39]
	global_store_dwordx4 v[132:133], v[32:35], off offset:96
	v_pk_fma_f32 v[38:39], v[62:63], v[40:41], v[42:43]
	global_load_dwordx4 v[32:35], v[134:135], off offset:128
	global_load_dwordx4 v[40:43], v[98:99], off offset:128
	s_waitcnt vmcnt(1)
	v_pk_mul_f32 v[32:33], v[32:33], 0.5 op_sel_hi:[1,0]
	global_store_dwordx4 v[98:99], v[36:39], off offset:96
	global_load_dwordx4 v[36:39], v[132:133], off offset:128
	s_waitcnt vmcnt(2)
	v_pk_fma_f32 v[0:1], v[0:1], v[32:33], v[40:41]
	s_waitcnt vmcnt(0)
	v_pk_fma_f32 v[16:17], v[16:17], v[32:33], v[36:37]
	v_pk_mul_f32 v[32:33], v[34:35], 0.5 op_sel_hi:[1,0]
	v_pk_fma_f32 v[2:3], v[2:3], v[32:33], v[42:43]
	v_pk_fma_f32 v[18:19], v[18:19], v[32:33], v[38:39]
	global_store_dwordx4 v[98:99], v[0:3], off offset:128
	global_load_dwordx4 v[0:3], v[134:135], off offset:160
	s_waitcnt vmcnt(0)
	v_pk_mul_f32 v[36:37], v[0:1], 0.5 op_sel_hi:[1,0]
	global_store_dwordx4 v[132:133], v[16:19], off offset:128
	global_load_dwordx4 v[16:19], v[132:133], off offset:160
	global_load_dwordx4 v[32:35], v[98:99], off offset:160
	s_waitcnt vmcnt(1)
	v_pk_fma_f32 v[0:1], v[20:21], v[36:37], v[16:17]
	v_pk_mul_f32 v[16:17], v[2:3], 0.5 op_sel_hi:[1,0]
	s_waitcnt vmcnt(0)
	v_pk_fma_f32 v[4:5], v[4:5], v[36:37], v[32:33]
	v_pk_fma_f32 v[2:3], v[22:23], v[16:17], v[18:19]
	global_store_dwordx4 v[132:133], v[0:3], off offset:160
	v_pk_fma_f32 v[6:7], v[6:7], v[16:17], v[34:35]
	global_load_dwordx4 v[0:3], v[134:135], off offset:192
	global_load_dwordx4 v[16:19], v[98:99], off offset:192
	s_waitcnt vmcnt(1)
	v_pk_mul_f32 v[20:21], v[0:1], 0.5 op_sel_hi:[1,0]
	global_store_dwordx4 v[98:99], v[4:7], off offset:160
	global_load_dwordx4 v[4:7], v[132:133], off offset:192
	s_waitcnt vmcnt(0)
	v_pk_fma_f32 v[0:1], v[24:25], v[20:21], v[4:5]
	v_pk_fma_f32 v[4:5], v[8:9], v[20:21], v[16:17]
	v_pk_mul_f32 v[8:9], v[2:3], 0.5 op_sel_hi:[1,0]
	v_pk_fma_f32 v[2:3], v[26:27], v[8:9], v[6:7]
	global_store_dwordx4 v[132:133], v[0:3], off offset:192
	v_pk_fma_f32 v[6:7], v[10:11], v[8:9], v[18:19]
	global_load_dwordx4 v[0:3], v[134:135], off offset:224
	global_load_dwordx4 v[16:19], v[98:99], off offset:224
	s_waitcnt vmcnt(1)
	v_pk_mul_f32 v[8:9], v[0:1], 0.5 op_sel_hi:[1,0]
	global_store_dwordx4 v[98:99], v[4:7], off offset:192
	global_load_dwordx4 v[4:7], v[132:133], off offset:224
	s_waitcnt vmcnt(0)
	v_pk_fma_f32 v[0:1], v[28:29], v[8:9], v[4:5]
	v_pk_fma_f32 v[4:5], v[12:13], v[8:9], v[16:17]
	v_pk_mul_f32 v[8:9], v[2:3], 0.5 op_sel_hi:[1,0]
	v_pk_fma_f32 v[2:3], v[30:31], v[8:9], v[6:7]
	v_pk_fma_f32 v[6:7], v[14:15], v[8:9], v[18:19]
	global_store_dwordx4 v[132:133], v[0:3], off offset:224
	global_store_dwordx4 v[98:99], v[4:7], off offset:224
	s_cbranch_vccnz .LBB0_336

.LBB0_328:
	s_ashr_i32 s40, s41, 31
	s_lshr_b32 s40, s40, 24
	s_add_i32 s40, s41, s40
	s_ashr_i32 s42, s40, 8
	s_lshl_b32 s43, s42, 5
	s_sub_i32 s43, 0x90, s43
	s_min_i32 s43, s43, 32
	s_abs_i32 s44, s43
	v_cvt_f32_u32_e32 v0, s44
	s_and_b32 s40, s40, 0xffffff00
	s_sub_i32 s45, s41, s40
	s_ashr_i32 s45, s45, 31
	v_rcp_iflag_f32_e32 v0, v0
	s_sub_i32 s40, s45, s40
	s_ashr_i32 s46, s43, 31
	s_add_i32 s40, s41, s40
	v_mul_f32_e32 v0, 0x4f7ffffe, v0
	v_cvt_u32_f32_e32 v0, v0
	s_xor_b32 s46, s45, s46
	s_xor_b32 s40, s40, s45
	s_sub_i32 s45, 0, s44
	v_readfirstlane_b32 s47, v0
	s_mul_i32 s45, s45, s47
	s_mul_hi_u32 s45, s47, s45
	s_add_i32 s47, s47, s45
	s_mul_hi_u32 s45, s40, s47
	s_mul_i32 s47, s45, s44
	s_sub_i32 s40, s40, s47
	s_add_i32 s47, s45, 1
	s_sub_i32 s48, s40, s44
	s_cmp_ge_u32 s40, s44
	s_cselect_b32 s45, s47, s45
	s_cselect_b32 s40, s48, s40
	s_add_i32 s47, s45, 1
	s_cmp_ge_u32 s40, s44
	s_cselect_b32 s40, s47, s45
	s_xor_b32 s40, s40, s46
	s_sub_i32 s40, s40, s46
	s_mul_i32 s43, s43, s40
	s_mulk_i32 s42, 0xe0
	s_add_i32 s43, s43, s42
	s_sub_i32 s41, s41, s43
	s_mul_i32 s42, s41, 0xb0000
	s_mul_hi_i32 s43, s41, 0xb0000
	s_add_u32 s42, s56, s42
	v_mov_b32_e32 v0, v162
	s_addc_u32 s43, s57, s43
	s_mul_i32 s44, s40, 0xb0000
	s_mul_hi_i32 s45, s40, 0xb0000
	v_lshlrev_b32_e32 v2, 3, v0
	s_add_u32 s44, s34, s44
	v_ashrrev_i32_e32 v1, 3, v0
	v_and_b32_e32 v2, 56, v2
	v_mov_b64_e32 v[4:5], s[42:43]
	s_addc_u32 s45, s27, s45
	v_mad_i64_i32 v[4:5], s[42:43], v1, s18, v[4:5]
	v_lshlrev_b32_e32 v96, 1, v2
	v_lshl_add_u64 v[148:149], v[4:5], 0, v[96:97]
	v_mov_b64_e32 v[4:5], s[44:45]
	v_mad_i64_i32 v[4:5], s[42:43], v1, s18, v[4:5]
	v_mad_u64_u32 v[2:3], s[42:43], v1, s84, v[2:3]
	v_lshl_add_u64 v[146:147], v[4:5], 0, v[96:97]
	s_andn2_b64 vcc, exec, s[38:39]
	v_lshl_add_u32 v209, v2, 1, 0
	s_cbranch_vccnz .LBB0_330
	v_add_co_u32_e32 v30, vcc, 0x2c000, v148
	s_nop 1
	v_addc_co_u32_e32 v31, vcc, 0, v149, vcc
	v_add_co_u32_e32 v32, vcc, 0x58000, v148
	s_nop 1
	v_addc_co_u32_e32 v33, vcc, 0, v149, vcc
	v_add_co_u32_e32 v34, vcc, 0x84000, v148
	s_nop 1
	v_addc_co_u32_e32 v35, vcc, 0, v149, vcc
	v_add_co_u32_e32 v36, vcc, s19, v146
	s_nop 1
	v_addc_co_u32_e32 v37, vcc, 0, v147, vcc
	v_add_co_u32_e32 v38, vcc, 0x58000, v146
	s_nop 1
	v_addc_co_u32_e32 v39, vcc, 0, v147, vcc
	v_add_co_u32_e32 v40, vcc, 0x84000, v146
	s_nop 1
	v_addc_co_u32_e32 v41, vcc, 0, v147, vcc
	global_load_dwordx4 v[2:5], v[40:41], off
	global_load_dwordx4 v[6:9], v[148:149], off
	global_load_dwordx4 v[100:103], v[148:149], off offset:128
	global_load_dwordx4 v[10:13], v[30:31], off
	global_load_dwordx4 v[104:107], v[30:31], off offset:128
	global_load_dwordx4 v[14:17], v[34:35], off
	global_load_dwordx4 v[108:111], v[34:35], off offset:128
	global_load_dwordx4 v[18:21], v[38:39], off
	global_load_dwordx4 v[120:123], v[38:39], off offset:128
	global_load_dwordx4 v[22:25], v[146:147], off
	global_load_dwordx4 v[64:67], v[148:149], off offset:256
	global_load_dwordx4 v[26:29], v[32:33], off
	global_load_dwordx4 v[68:71], v[30:31], off offset:256
	global_load_dwordx4 v[112:115], v[32:33], off offset:128
	global_load_dwordx4 v[72:75], v[32:33], off offset:256
	global_load_dwordx4 v[30:33], v[36:37], off
	global_load_dwordx4 v[76:79], v[34:35], off offset:256
	global_load_dwordx4 v[116:119], v[146:147], off offset:128
	global_load_dwordx4 v[80:83], v[146:147], off offset:256
	global_load_dwordx4 v[124:127], v[36:37], off offset:128
	global_load_dwordx4 v[84:87], v[36:37], off offset:256
	global_load_dwordx4 v[88:91], v[38:39], off offset:256
	global_load_dwordx4 v[128:131], v[40:41], off offset:128
	global_load_dwordx4 v[92:95], v[40:41], off offset:256
	s_waitcnt vmcnt(22)
	ds_write_b128 v209, v[6:9]
	s_waitcnt vmcnt(14)
	ds_write_b128 v209, v[22:25] offset:36864
	ds_write_b128 v209, v[10:13] offset:4608
	s_waitcnt vmcnt(12)
	ds_write_b128 v209, v[26:29] offset:9216
	ds_write_b128 v209, v[14:17] offset:13824
	s_waitcnt vmcnt(8)
	ds_write_b128 v209, v[30:33] offset:41472
	ds_write_b128 v209, v[18:21] offset:46080
	ds_write_b128 v209, v[2:5] offset:50688
	s_waitcnt lgkmcnt(0)
	s_barrier
.LBB0_330:
	v_mad_i64_i32 v[2:3], s[38:39], v1, s18, 0
	s_add_u32 s38, s56, s6
	s_addc_u32 s39, s57, s7
	s_and_b64 s[6:7], s[2:3], exec
	s_cselect_b32 s7, s39, 0
	s_cselect_b32 s6, s38, 0
	s_add_u32 s38, s34, s12
	s_addc_u32 s39, s27, s13
	s_and_b64 s[12:13], s[2:3], exec
	s_cselect_b32 s13, s39, 0
	s_cselect_b32 s12, s38, 0
	v_lshl_add_u64 v[4:5], s[6:7], 0, v[2:3]
	v_lshl_add_u64 v[2:3], s[12:13], 0, v[2:3]
	v_lshl_add_u64 v[170:171], v[2:3], 0, v[96:97]
	v_lshrrev_b32_e32 v1, 1, v0
	v_and_b32_e32 v2, 31, v0
	v_and_or_b32 v1, v1, s81, v2
	v_lshrrev_b32_e32 v2, 2, v0
	v_and_b32_e32 v2, 8, v2
	v_and_b32_e32 v0, 0x5f, v0
	v_lshl_add_u64 v[172:173], v[4:5], 0, v[96:97]
	v_mad_u64_u32 v[4:5], s[6:7], v1, s84, v[2:3]
	v_mad_u32_u24 v0, v0, s84, v2
	v_lshl_add_u32 v210, v4, 1, 0
	v_lshl_add_u32 v96, v0, 1, 0
	v_add_u32_e32 v211, 0xd800, v209
	s_setprio 1
	ds_read_b128 v[212:215], v96 offset:36864
	ds_read_b128 v[216:219], v210
	ds_read_b128 v[220:223], v210 offset:4608
	ds_read_b128 v[224:227], v96 offset:36896
	ds_read_b128 v[228:231], v210 offset:32
	ds_read_b128 v[244:247], v210 offset:4640
	ds_read_b128 v[252:255], v96 offset:41472
	s_waitcnt lgkmcnt(5)
	v_mfma_f32_32x32x16_bf16 v[32:47], v[212:215], v[216:219], 0
	s_waitcnt lgkmcnt(4)
	v_mfma_f32_32x32x16_bf16 v[48:63], v[212:215], v[220:223], 0
	ds_read_b128 v[212:215], v96 offset:41504
	s_waitcnt lgkmcnt(3)
	v_mfma_f32_32x32x16_bf16 v[32:47], v[224:227], v[228:231], v[32:47]
	s_waitcnt lgkmcnt(2)
	v_mfma_f32_32x32x16_bf16 v[48:63], v[224:227], v[244:247], v[48:63]
	ds_read_b128 v[224:227], v96 offset:36928
	s_waitcnt lgkmcnt(2)
	v_mfma_f32_32x32x16_bf16 v[16:31], v[252:255], v[216:219], 0
	ds_read_b128 v[216:219], v210 offset:64
	v_mfma_f32_32x32x16_bf16 v[0:15], v[252:255], v[220:223], 0
	ds_read_b128 v[252:255], v210 offset:4672
	ds_read_b128 v[220:223], v96 offset:41536
	s_waitcnt lgkmcnt(4)
	v_mfma_f32_32x32x16_bf16 v[16:31], v[212:215], v[228:231], v[16:31]
	ds_read_b128 v[228:231], v96 offset:36960
	v_mfma_f32_32x32x16_bf16 v[0:15], v[212:215], v[244:247], v[0:15]
	ds_read_b128 v[212:215], v210 offset:96
	ds_read_b128 v[244:247], v210 offset:4704
	s_waitcnt lgkmcnt(5)
	v_mfma_f32_32x32x16_bf16 v[32:47], v[224:227], v[216:219], v[32:47]
	v_add_co_u32_e32 v150, vcc, s19, v148
	ds_write_b128 v209, v[100:103] offset:18432
	ds_write_b128 v209, v[104:107] offset:23040
	s_waitcnt lgkmcnt(6)
	v_mfma_f32_32x32x16_bf16 v[48:63], v[224:227], v[252:255], v[48:63]
	ds_read_b128 v[224:227], v96 offset:41568
	ds_write_b128 v209, v[112:115] offset:27648
	ds_write_b128 v209, v[108:111] offset:32256
	s_waitcnt vmcnt(6)
	ds_write_b128 v209, v[116:119] offset:55296
	s_waitcnt lgkmcnt(9)
	v_mfma_f32_32x32x16_bf16 v[16:31], v[220:223], v[216:219], v[16:31]
	s_waitcnt vmcnt(4)
	ds_write_b128 v209, v[124:127] offset:59904
	ds_write_b128 v209, v[120:123] offset:64512
	v_mfma_f32_32x32x16_bf16 v[0:15], v[220:223], v[252:255], v[0:15]
	s_waitcnt vmcnt(1)
	ds_write_b128 v211, v[128:131] offset:13824
	v_addc_co_u32_e32 v151, vcc, 0, v149, vcc
	v_add_co_u32_e32 v152, vcc, s20, v148
	global_load_dwordx4 v[98:101], v[148:149], off offset:384
	s_waitcnt lgkmcnt(10)
	v_mfma_f32_32x32x16_bf16 v[32:47], v[228:231], v[212:215], v[32:47]
	global_load_dwordx4 v[102:105], v[150:151], off offset:384
	v_addc_co_u32_e32 v153, vcc, 0, v149, vcc
	v_add_co_u32_e32 v154, vcc, s21, v148
	global_load_dwordx4 v[106:109], v[152:153], off offset:384
	s_waitcnt lgkmcnt(9)
	v_mfma_f32_32x32x16_bf16 v[48:63], v[228:231], v[244:247], v[48:63]
	s_nop 0
	v_addc_co_u32_e32 v155, vcc, 0, v149, vcc
	v_add_co_u32_e32 v156, vcc, s19, v146
	global_load_dwordx4 v[110:113], v[154:155], off offset:384
	global_load_dwordx4 v[114:117], v[146:147], off offset:384
	s_waitcnt lgkmcnt(6)
	v_mfma_f32_32x32x16_bf16 v[16:31], v[224:227], v[212:215], v[16:31]
	v_addc_co_u32_e32 v157, vcc, 0, v147, vcc
	v_add_co_u32_e32 v158, vcc, s20, v146
	global_load_dwordx4 v[118:121], v[156:157], off offset:384
	s_nop 0
	v_addc_co_u32_e32 v159, vcc, 0, v147, vcc
	v_add_co_u32_e32 v160, vcc, s21, v146
	v_mfma_f32_32x32x16_bf16 v[0:15], v[224:227], v[244:247], v[0:15]
	global_load_dwordx4 v[122:125], v[158:159], off offset:384
	s_nop 0
	v_addc_co_u32_e32 v161, vcc, 0, v147, vcc
	global_load_dwordx4 v[130:133], v[160:161], off offset:384
	s_setprio 0
	s_waitcnt lgkmcnt(0)
	s_barrier
	s_setprio 1
	ds_read_b128 v[212:215], v96 offset:55296
	ds_read_b128 v[216:219], v210 offset:18432
	ds_read_b128 v[220:223], v210 offset:23040
	ds_read_b128 v[224:227], v96 offset:59904
	ds_read_b128 v[228:231], v96 offset:55328
	ds_read_b128 v[244:247], v210 offset:18464
	ds_read_b128 v[252:255], v210 offset:23072
	s_waitcnt lgkmcnt(5)
	v_mfma_f32_32x32x16_bf16 v[32:47], v[212:215], v[216:219], v[32:47]
	s_waitcnt lgkmcnt(4)
	v_mfma_f32_32x32x16_bf16 v[48:63], v[212:215], v[220:223], v[48:63]
	ds_read_b128 v[212:215], v96 offset:59936
	s_waitcnt lgkmcnt(4)
	v_mfma_f32_32x32x16_bf16 v[16:31], v[224:227], v[216:219], v[16:31]
	ds_read_b128 v[216:219], v96 offset:55360
	v_mfma_f32_32x32x16_bf16 v[0:15], v[224:227], v[220:223], v[0:15]
	ds_read_b128 v[224:227], v210 offset:18496
	ds_read_b128 v[220:223], v210 offset:23104
	s_waitcnt lgkmcnt(5)
	v_mfma_f32_32x32x16_bf16 v[32:47], v[228:231], v[244:247], v[32:47]
	s_waitcnt lgkmcnt(4)
	v_mfma_f32_32x32x16_bf16 v[48:63], v[228:231], v[252:255], v[48:63]
	ds_read_b128 v[228:231], v96 offset:59968
	s_waitcnt lgkmcnt(4)
	v_mfma_f32_32x32x16_bf16 v[16:31], v[212:215], v[244:247], v[16:31]
	ds_read_b128 v[244:247], v96 offset:55392
	v_mfma_f32_32x32x16_bf16 v[0:15], v[212:215], v[252:255], v[0:15]
	ds_read_b128 v[212:215], v210 offset:18528
	ds_read_b128 v[252:255], v210 offset:23136
	s_waitcnt lgkmcnt(5)
	v_mfma_f32_32x32x16_bf16 v[32:47], v[216:219], v[224:227], v[32:47]
	ds_write_b128 v209, v[64:67]
	ds_write_b128 v209, v[68:71] offset:4608
	s_waitcnt lgkmcnt(6)
	v_mfma_f32_32x32x16_bf16 v[48:63], v[216:219], v[220:223], v[48:63]
	ds_read_b128 v[216:219], v96 offset:60000
	ds_write_b128 v209, v[72:75] offset:9216
	ds_write_b128 v209, v[76:79] offset:13824
	s_waitcnt lgkmcnt(8)
	v_mfma_f32_32x32x16_bf16 v[16:31], v[228:231], v[224:227], v[16:31]
	ds_write_b128 v209, v[80:83] offset:36864
	ds_write_b128 v209, v[84:87] offset:41472
	v_mfma_f32_32x32x16_bf16 v[0:15], v[228:231], v[220:223], v[0:15]
	ds_write_b128 v209, v[88:91] offset:46080
	s_waitcnt lgkmcnt(9)
	v_mfma_f32_32x32x16_bf16 v[32:47], v[244:247], v[212:215], v[32:47]
	s_waitcnt vmcnt(8)
	ds_write_b128 v209, v[92:95] offset:50688
	global_load_dwordx4 v[64:67], v[148:149], off offset:512
	s_waitcnt lgkmcnt(9)
	v_mfma_f32_32x32x16_bf16 v[48:63], v[244:247], v[252:255], v[48:63]
	global_load_dwordx4 v[72:75], v[150:151], off offset:512
	global_load_dwordx4 v[76:79], v[152:153], off offset:512
	s_waitcnt lgkmcnt(6)
	v_mfma_f32_32x32x16_bf16 v[16:31], v[216:219], v[212:215], v[16:31]
	global_load_dwordx4 v[80:83], v[154:155], off offset:512
	global_load_dwordx4 v[126:129], v[146:147], off offset:512
	global_load_dwordx4 v[134:137], v[156:157], off offset:512
	v_mfma_f32_32x32x16_bf16 v[0:15], v[216:219], v[252:255], v[0:15]
	global_load_dwordx4 v[138:141], v[158:159], off offset:512
	global_load_dwordx4 v[142:145], v[160:161], off offset:512
	s_setprio 0
	s_waitcnt lgkmcnt(0)
	s_barrier
	s_setprio 1
	ds_read_b128 v[212:215], v96 offset:36864
	ds_read_b128 v[216:219], v210
	ds_read_b128 v[220:223], v210 offset:4608
	ds_read_b128 v[224:227], v96 offset:41472
	ds_read_b128 v[228:231], v96 offset:36896
	ds_read_b128 v[244:247], v210 offset:32
	ds_read_b128 v[252:255], v210 offset:4640
	s_waitcnt lgkmcnt(5)
	v_mfma_f32_32x32x16_bf16 v[32:47], v[212:215], v[216:219], v[32:47]
	s_waitcnt lgkmcnt(4)
	v_mfma_f32_32x32x16_bf16 v[48:63], v[212:215], v[220:223], v[48:63]
	ds_read_b128 v[212:215], v96 offset:41504
	s_waitcnt lgkmcnt(4)
	v_mfma_f32_32x32x16_bf16 v[16:31], v[224:227], v[216:219], v[16:31]
	ds_read_b128 v[216:219], v96 offset:36928
	v_mfma_f32_32x32x16_bf16 v[0:15], v[224:227], v[220:223], v[0:15]
	ds_read_b128 v[224:227], v210 offset:64
	ds_read_b128 v[220:223], v210 offset:4672
	s_waitcnt lgkmcnt(5)
	v_mfma_f32_32x32x16_bf16 v[32:47], v[228:231], v[244:247], v[32:47]
	s_waitcnt lgkmcnt(4)
	v_mfma_f32_32x32x16_bf16 v[48:63], v[228:231], v[252:255], v[48:63]
	ds_read_b128 v[228:231], v96 offset:41536
	s_waitcnt lgkmcnt(4)
	v_mfma_f32_32x32x16_bf16 v[16:31], v[212:215], v[244:247], v[16:31]
	ds_read_b128 v[244:247], v96 offset:36960
	v_mfma_f32_32x32x16_bf16 v[0:15], v[212:215], v[252:255], v[0:15]
	ds_read_b128 v[212:215], v210 offset:96
	ds_read_b128 v[252:255], v210 offset:4704
	s_waitcnt lgkmcnt(5)
	v_mfma_f32_32x32x16_bf16 v[32:47], v[216:219], v[224:227], v[32:47]
	s_waitcnt vmcnt(15)
	ds_write_b128 v209, v[98:101] offset:18432
	global_load_dwordx4 v[68:71], v[148:149], off offset:640
	s_waitcnt lgkmcnt(5)
	v_mfma_f32_32x32x16_bf16 v[48:63], v[216:219], v[220:223], v[48:63]
	ds_read_b128 v[216:219], v96 offset:41568
	s_waitcnt vmcnt(15)
	ds_write_b128 v209, v[102:105] offset:23040
	global_load_dwordx4 v[84:87], v[150:151], off offset:640
	s_waitcnt lgkmcnt(6)
	v_mfma_f32_32x32x16_bf16 v[16:31], v[228:231], v[224:227], v[16:31]
	s_waitcnt vmcnt(15)
	ds_write_b128 v209, v[106:109] offset:27648
	global_load_dwordx4 v[88:91], v[152:153], off offset:640
	v_mfma_f32_32x32x16_bf16 v[0:15], v[228:231], v[220:223], v[0:15]
	s_waitcnt vmcnt(15)
	ds_write_b128 v209, v[110:113] offset:32256
	global_load_dwordx4 v[92:95], v[154:155], off offset:640
	s_waitcnt lgkmcnt(6)
	v_mfma_f32_32x32x16_bf16 v[32:47], v[244:247], v[212:215], v[32:47]
	s_waitcnt vmcnt(15)
	ds_write_b128 v209, v[114:117] offset:55296
	global_load_dwordx4 v[98:101], v[146:147], off offset:640
	s_waitcnt lgkmcnt(6)
	v_mfma_f32_32x32x16_bf16 v[48:63], v[244:247], v[252:255], v[48:63]
	s_waitcnt vmcnt(15)
	ds_write_b128 v209, v[118:121] offset:59904
	global_load_dwordx4 v[106:109], v[156:157], off offset:640
	s_waitcnt lgkmcnt(5)
	v_mfma_f32_32x32x16_bf16 v[16:31], v[216:219], v[212:215], v[16:31]
	s_waitcnt vmcnt(15)
	ds_write_b128 v209, v[122:125] offset:64512
	global_load_dwordx4 v[110:113], v[158:159], off offset:640
	v_mfma_f32_32x32x16_bf16 v[0:15], v[216:219], v[252:255], v[0:15]
	s_waitcnt vmcnt(15)
	ds_write_b128 v211, v[130:133] offset:13824
	global_load_dwordx4 v[114:117], v[160:161], off offset:640
	s_setprio 0
	s_waitcnt lgkmcnt(0)
	s_barrier
	s_setprio 1
	ds_read_b128 v[212:215], v96 offset:55296
	ds_read_b128 v[216:219], v210 offset:18432
	ds_read_b128 v[220:223], v210 offset:23040
	ds_read_b128 v[224:227], v96 offset:59904
	ds_read_b128 v[228:231], v96 offset:55328
	ds_read_b128 v[244:247], v210 offset:18464
	ds_read_b128 v[252:255], v210 offset:23072
	s_waitcnt lgkmcnt(5)
	v_mfma_f32_32x32x16_bf16 v[32:47], v[212:215], v[216:219], v[32:47]
	s_waitcnt lgkmcnt(4)
	v_mfma_f32_32x32x16_bf16 v[48:63], v[212:215], v[220:223], v[48:63]
	ds_read_b128 v[212:215], v96 offset:59936
	s_waitcnt lgkmcnt(4)
	v_mfma_f32_32x32x16_bf16 v[16:31], v[224:227], v[216:219], v[16:31]
	ds_read_b128 v[216:219], v96 offset:55360
	v_mfma_f32_32x32x16_bf16 v[0:15], v[224:227], v[220:223], v[0:15]
	ds_read_b128 v[224:227], v210 offset:18496
	ds_read_b128 v[220:223], v210 offset:23104
	s_waitcnt lgkmcnt(5)
	v_mfma_f32_32x32x16_bf16 v[32:47], v[228:231], v[244:247], v[32:47]
	s_waitcnt lgkmcnt(4)
	v_mfma_f32_32x32x16_bf16 v[48:63], v[228:231], v[252:255], v[48:63]
	ds_read_b128 v[228:231], v96 offset:59968
	s_waitcnt lgkmcnt(4)
	v_mfma_f32_32x32x16_bf16 v[16:31], v[212:215], v[244:247], v[16:31]
	ds_read_b128 v[244:247], v96 offset:55392
	v_mfma_f32_32x32x16_bf16 v[0:15], v[212:215], v[252:255], v[0:15]
	ds_read_b128 v[212:215], v210 offset:18528
	ds_read_b128 v[252:255], v210 offset:23136
	s_waitcnt lgkmcnt(5)
	v_mfma_f32_32x32x16_bf16 v[32:47], v[216:219], v[224:227], v[32:47]
	s_waitcnt vmcnt(15)
	ds_write_b128 v209, v[64:67]
	global_load_dwordx4 v[64:67], v[148:149], off offset:768
	s_waitcnt lgkmcnt(5)
	v_mfma_f32_32x32x16_bf16 v[48:63], v[216:219], v[220:223], v[48:63]
	ds_read_b128 v[216:219], v96 offset:60000
	s_waitcnt vmcnt(15)
	ds_write_b128 v209, v[72:75] offset:4608
	global_load_dwordx4 v[72:75], v[150:151], off offset:768
	s_waitcnt lgkmcnt(6)
	v_mfma_f32_32x32x16_bf16 v[16:31], v[228:231], v[224:227], v[16:31]
	s_waitcnt vmcnt(15)
	ds_write_b128 v209, v[76:79] offset:9216
	global_load_dwordx4 v[76:79], v[152:153], off offset:768
	v_mfma_f32_32x32x16_bf16 v[0:15], v[228:231], v[220:223], v[0:15]
	s_waitcnt vmcnt(15)
	ds_write_b128 v209, v[80:83] offset:13824
	global_load_dwordx4 v[80:83], v[154:155], off offset:768
	s_waitcnt lgkmcnt(6)
	v_mfma_f32_32x32x16_bf16 v[32:47], v[244:247], v[212:215], v[32:47]
	s_waitcnt vmcnt(15)
	ds_write_b128 v209, v[126:129] offset:36864
	global_load_dwordx4 v[102:105], v[146:147], off offset:768
	s_waitcnt lgkmcnt(6)
	v_mfma_f32_32x32x16_bf16 v[48:63], v[244:247], v[252:255], v[48:63]
	s_waitcnt vmcnt(15)
	ds_write_b128 v209, v[134:137] offset:41472
	global_load_dwordx4 v[118:121], v[156:157], off offset:768
	s_waitcnt lgkmcnt(5)
	v_mfma_f32_32x32x16_bf16 v[16:31], v[216:219], v[212:215], v[16:31]
	s_waitcnt vmcnt(15)
	ds_write_b128 v209, v[138:141] offset:46080
	global_load_dwordx4 v[122:125], v[158:159], off offset:768
	v_mfma_f32_32x32x16_bf16 v[0:15], v[216:219], v[252:255], v[0:15]
	s_waitcnt vmcnt(15)
	ds_write_b128 v209, v[142:145] offset:50688
	global_load_dwordx4 v[126:129], v[160:161], off offset:768
	s_setprio 0
	s_waitcnt lgkmcnt(0)
	s_barrier
	s_setprio 1
	ds_read_b128 v[212:215], v96 offset:36864
	ds_read_b128 v[216:219], v210
	ds_read_b128 v[220:223], v210 offset:4608
	ds_read_b128 v[224:227], v96 offset:41472
	ds_read_b128 v[228:231], v96 offset:36896
	ds_read_b128 v[244:247], v210 offset:32
	ds_read_b128 v[252:255], v210 offset:4640
	s_waitcnt lgkmcnt(5)
	v_mfma_f32_32x32x16_bf16 v[32:47], v[212:215], v[216:219], v[32:47]
	s_waitcnt lgkmcnt(4)
	v_mfma_f32_32x32x16_bf16 v[48:63], v[212:215], v[220:223], v[48:63]
	ds_read_b128 v[212:215], v96 offset:41504
	s_waitcnt lgkmcnt(4)
	v_mfma_f32_32x32x16_bf16 v[16:31], v[224:227], v[216:219], v[16:31]
	ds_read_b128 v[216:219], v96 offset:36928
	v_mfma_f32_32x32x16_bf16 v[0:15], v[224:227], v[220:223], v[0:15]
	ds_read_b128 v[224:227], v210 offset:64
	ds_read_b128 v[220:223], v210 offset:4672
	s_waitcnt lgkmcnt(5)
	v_mfma_f32_32x32x16_bf16 v[32:47], v[228:231], v[244:247], v[32:47]
	s_waitcnt lgkmcnt(4)
	v_mfma_f32_32x32x16_bf16 v[48:63], v[228:231], v[252:255], v[48:63]
	ds_read_b128 v[228:231], v96 offset:41536
	s_waitcnt lgkmcnt(4)
	v_mfma_f32_32x32x16_bf16 v[16:31], v[212:215], v[244:247], v[16:31]
	ds_read_b128 v[244:247], v96 offset:36960
	v_mfma_f32_32x32x16_bf16 v[0:15], v[212:215], v[252:255], v[0:15]
	ds_read_b128 v[212:215], v210 offset:96
	ds_read_b128 v[252:255], v210 offset:4704
	s_waitcnt lgkmcnt(5)
	v_mfma_f32_32x32x16_bf16 v[32:47], v[216:219], v[224:227], v[32:47]
	s_waitcnt vmcnt(15)
	ds_write_b128 v209, v[68:71] offset:18432
	global_load_dwordx4 v[68:71], v[148:149], off offset:896
	s_waitcnt lgkmcnt(5)
	v_mfma_f32_32x32x16_bf16 v[48:63], v[216:219], v[220:223], v[48:63]
	ds_read_b128 v[216:219], v96 offset:41568
	s_waitcnt vmcnt(15)
	ds_write_b128 v209, v[84:87] offset:23040
	global_load_dwordx4 v[84:87], v[150:151], off offset:896
	s_waitcnt lgkmcnt(6)
	v_mfma_f32_32x32x16_bf16 v[16:31], v[228:231], v[224:227], v[16:31]
	s_waitcnt vmcnt(15)
	ds_write_b128 v209, v[88:91] offset:27648
	global_load_dwordx4 v[88:91], v[152:153], off offset:896
	v_mfma_f32_32x32x16_bf16 v[0:15], v[228:231], v[220:223], v[0:15]
	s_waitcnt vmcnt(15)
	ds_write_b128 v209, v[92:95] offset:32256
	global_load_dwordx4 v[92:95], v[154:155], off offset:896
	s_waitcnt lgkmcnt(6)
	v_mfma_f32_32x32x16_bf16 v[32:47], v[244:247], v[212:215], v[32:47]
	s_waitcnt vmcnt(15)
	ds_write_b128 v209, v[98:101] offset:55296
	global_load_dwordx4 v[98:101], v[146:147], off offset:896
	s_waitcnt lgkmcnt(6)
	v_mfma_f32_32x32x16_bf16 v[48:63], v[244:247], v[252:255], v[48:63]
	s_waitcnt vmcnt(15)
	ds_write_b128 v209, v[106:109] offset:59904
	global_load_dwordx4 v[106:109], v[156:157], off offset:896
	s_waitcnt lgkmcnt(5)
	v_mfma_f32_32x32x16_bf16 v[16:31], v[216:219], v[212:215], v[16:31]
	s_waitcnt vmcnt(15)
	ds_write_b128 v209, v[110:113] offset:64512
	global_load_dwordx4 v[110:113], v[158:159], off offset:896
	v_mfma_f32_32x32x16_bf16 v[0:15], v[216:219], v[252:255], v[0:15]
	s_waitcnt vmcnt(15)
	ds_write_b128 v211, v[114:117] offset:13824
	global_load_dwordx4 v[114:117], v[160:161], off offset:896
	s_setprio 0
	s_waitcnt lgkmcnt(0)
	s_barrier
	s_setprio 1
	ds_read_b128 v[212:215], v96 offset:55296
	ds_read_b128 v[216:219], v210 offset:18432
	ds_read_b128 v[220:223], v210 offset:23040
	ds_read_b128 v[224:227], v96 offset:59904
	ds_read_b128 v[228:231], v96 offset:55328
	ds_read_b128 v[244:247], v210 offset:18464
	ds_read_b128 v[252:255], v210 offset:23072
	s_waitcnt lgkmcnt(5)
	v_mfma_f32_32x32x16_bf16 v[32:47], v[212:215], v[216:219], v[32:47]
	s_waitcnt lgkmcnt(4)
	v_mfma_f32_32x32x16_bf16 v[48:63], v[212:215], v[220:223], v[48:63]
	ds_read_b128 v[212:215], v96 offset:59936
	s_waitcnt lgkmcnt(4)
	v_mfma_f32_32x32x16_bf16 v[16:31], v[224:227], v[216:219], v[16:31]
	ds_read_b128 v[216:219], v96 offset:55360
	v_mfma_f32_32x32x16_bf16 v[0:15], v[224:227], v[220:223], v[0:15]
	ds_read_b128 v[224:227], v210 offset:18496
	ds_read_b128 v[220:223], v210 offset:23104
	s_waitcnt lgkmcnt(5)
	v_mfma_f32_32x32x16_bf16 v[32:47], v[228:231], v[244:247], v[32:47]
	s_waitcnt lgkmcnt(4)
	v_mfma_f32_32x32x16_bf16 v[48:63], v[228:231], v[252:255], v[48:63]
	ds_read_b128 v[228:231], v96 offset:59968
	s_waitcnt lgkmcnt(4)
	v_mfma_f32_32x32x16_bf16 v[16:31], v[212:215], v[244:247], v[16:31]
	ds_read_b128 v[244:247], v96 offset:55392
	v_mfma_f32_32x32x16_bf16 v[0:15], v[212:215], v[252:255], v[0:15]
	ds_read_b128 v[212:215], v210 offset:18528
	ds_read_b128 v[252:255], v210 offset:23136
	s_waitcnt lgkmcnt(5)
	v_mfma_f32_32x32x16_bf16 v[32:47], v[216:219], v[224:227], v[32:47]
	s_waitcnt vmcnt(15)
	ds_write_b128 v209, v[64:67]
	global_load_dwordx4 v[64:67], v[148:149], off offset:1024
	s_waitcnt lgkmcnt(5)
	v_mfma_f32_32x32x16_bf16 v[48:63], v[216:219], v[220:223], v[48:63]
	ds_read_b128 v[216:219], v96 offset:60000
	s_waitcnt vmcnt(15)
	ds_write_b128 v209, v[72:75] offset:4608
	global_load_dwordx4 v[72:75], v[150:151], off offset:1024
	s_waitcnt lgkmcnt(6)
	v_mfma_f32_32x32x16_bf16 v[16:31], v[228:231], v[224:227], v[16:31]
	s_waitcnt vmcnt(15)
	ds_write_b128 v209, v[76:79] offset:9216
	global_load_dwordx4 v[76:79], v[152:153], off offset:1024
	v_mfma_f32_32x32x16_bf16 v[0:15], v[228:231], v[220:223], v[0:15]
	s_waitcnt vmcnt(15)
	ds_write_b128 v209, v[80:83] offset:13824
	global_load_dwordx4 v[80:83], v[154:155], off offset:1024
	s_waitcnt lgkmcnt(6)
	v_mfma_f32_32x32x16_bf16 v[32:47], v[244:247], v[212:215], v[32:47]
	s_waitcnt vmcnt(15)
	ds_write_b128 v209, v[102:105] offset:36864
	global_load_dwordx4 v[102:105], v[146:147], off offset:1024
	s_waitcnt lgkmcnt(6)
	v_mfma_f32_32x32x16_bf16 v[48:63], v[244:247], v[252:255], v[48:63]
	s_waitcnt vmcnt(15)
	ds_write_b128 v209, v[118:121] offset:41472
	global_load_dwordx4 v[118:121], v[156:157], off offset:1024
	s_waitcnt lgkmcnt(5)
	v_mfma_f32_32x32x16_bf16 v[16:31], v[216:219], v[212:215], v[16:31]
	s_waitcnt vmcnt(15)
	ds_write_b128 v209, v[122:125] offset:46080
	global_load_dwordx4 v[122:125], v[158:159], off offset:1024
	v_mfma_f32_32x32x16_bf16 v[0:15], v[216:219], v[252:255], v[0:15]
	s_waitcnt vmcnt(15)
	ds_write_b128 v209, v[126:129] offset:50688
	global_load_dwordx4 v[126:129], v[160:161], off offset:1024
	s_setprio 0
	s_waitcnt lgkmcnt(0)
	s_barrier
	s_setprio 1
	ds_read_b128 v[212:215], v96 offset:36864
	ds_read_b128 v[216:219], v210
	ds_read_b128 v[220:223], v210 offset:4608
	ds_read_b128 v[224:227], v96 offset:41472
	ds_read_b128 v[228:231], v96 offset:36896
	ds_read_b128 v[244:247], v210 offset:32
	ds_read_b128 v[252:255], v210 offset:4640
	s_waitcnt lgkmcnt(5)
	v_mfma_f32_32x32x16_bf16 v[32:47], v[212:215], v[216:219], v[32:47]
	s_waitcnt lgkmcnt(4)
	v_mfma_f32_32x32x16_bf16 v[48:63], v[212:215], v[220:223], v[48:63]
	ds_read_b128 v[212:215], v96 offset:41504
	s_waitcnt lgkmcnt(4)
	v_mfma_f32_32x32x16_bf16 v[16:31], v[224:227], v[216:219], v[16:31]
	ds_read_b128 v[216:219], v96 offset:36928
	v_mfma_f32_32x32x16_bf16 v[0:15], v[224:227], v[220:223], v[0:15]
	ds_read_b128 v[224:227], v210 offset:64
	ds_read_b128 v[220:223], v210 offset:4672
	s_waitcnt lgkmcnt(5)
	v_mfma_f32_32x32x16_bf16 v[32:47], v[228:231], v[244:247], v[32:47]
	s_waitcnt lgkmcnt(4)
	v_mfma_f32_32x32x16_bf16 v[48:63], v[228:231], v[252:255], v[48:63]
	ds_read_b128 v[228:231], v96 offset:41536
	s_waitcnt lgkmcnt(4)
	v_mfma_f32_32x32x16_bf16 v[16:31], v[212:215], v[244:247], v[16:31]
	ds_read_b128 v[244:247], v96 offset:36960
	v_mfma_f32_32x32x16_bf16 v[0:15], v[212:215], v[252:255], v[0:15]
	ds_read_b128 v[212:215], v210 offset:96
	ds_read_b128 v[252:255], v210 offset:4704
	s_waitcnt lgkmcnt(5)
	v_mfma_f32_32x32x16_bf16 v[32:47], v[216:219], v[224:227], v[32:47]
	s_waitcnt vmcnt(15)
	ds_write_b128 v209, v[68:71] offset:18432
	global_load_dwordx4 v[68:71], v[148:149], off offset:1152
	s_waitcnt lgkmcnt(5)
	v_mfma_f32_32x32x16_bf16 v[48:63], v[216:219], v[220:223], v[48:63]
	ds_read_b128 v[216:219], v96 offset:41568
	s_waitcnt vmcnt(15)
	ds_write_b128 v209, v[84:87] offset:23040
	global_load_dwordx4 v[84:87], v[150:151], off offset:1152
	s_waitcnt lgkmcnt(6)
	v_mfma_f32_32x32x16_bf16 v[16:31], v[228:231], v[224:227], v[16:31]
	s_waitcnt vmcnt(15)
	ds_write_b128 v209, v[88:91] offset:27648
	global_load_dwordx4 v[88:91], v[152:153], off offset:1152
	v_mfma_f32_32x32x16_bf16 v[0:15], v[228:231], v[220:223], v[0:15]
	s_waitcnt vmcnt(15)
	ds_write_b128 v209, v[92:95] offset:32256
	global_load_dwordx4 v[92:95], v[154:155], off offset:1152
	s_waitcnt lgkmcnt(6)
	v_mfma_f32_32x32x16_bf16 v[32:47], v[244:247], v[212:215], v[32:47]
	s_waitcnt vmcnt(15)
	ds_write_b128 v209, v[98:101] offset:55296
	global_load_dwordx4 v[98:101], v[146:147], off offset:1152
	s_waitcnt lgkmcnt(6)
	v_mfma_f32_32x32x16_bf16 v[48:63], v[244:247], v[252:255], v[48:63]
	s_waitcnt vmcnt(15)
	ds_write_b128 v209, v[106:109] offset:59904
	global_load_dwordx4 v[106:109], v[156:157], off offset:1152
	s_waitcnt lgkmcnt(5)
	v_mfma_f32_32x32x16_bf16 v[16:31], v[216:219], v[212:215], v[16:31]
	s_waitcnt vmcnt(15)
	ds_write_b128 v209, v[110:113] offset:64512
	global_load_dwordx4 v[110:113], v[158:159], off offset:1152
	v_mfma_f32_32x32x16_bf16 v[0:15], v[216:219], v[252:255], v[0:15]
	s_waitcnt vmcnt(15)
	ds_write_b128 v211, v[114:117] offset:13824
	global_load_dwordx4 v[114:117], v[160:161], off offset:1152
	s_setprio 0
	s_waitcnt lgkmcnt(0)
	s_barrier
	s_setprio 1
	ds_read_b128 v[212:215], v96 offset:55296
	ds_read_b128 v[216:219], v210 offset:18432
	ds_read_b128 v[220:223], v210 offset:23040
	ds_read_b128 v[224:227], v96 offset:59904
	ds_read_b128 v[228:231], v96 offset:55328
	ds_read_b128 v[244:247], v210 offset:18464
	ds_read_b128 v[252:255], v210 offset:23072
	s_waitcnt lgkmcnt(5)
	v_mfma_f32_32x32x16_bf16 v[32:47], v[212:215], v[216:219], v[32:47]
	s_waitcnt lgkmcnt(4)
	v_mfma_f32_32x32x16_bf16 v[48:63], v[212:215], v[220:223], v[48:63]
	ds_read_b128 v[212:215], v96 offset:59936
	s_waitcnt lgkmcnt(4)
	v_mfma_f32_32x32x16_bf16 v[16:31], v[224:227], v[216:219], v[16:31]
	ds_read_b128 v[216:219], v96 offset:55360
	v_mfma_f32_32x32x16_bf16 v[0:15], v[224:227], v[220:223], v[0:15]
	ds_read_b128 v[224:227], v210 offset:18496
	ds_read_b128 v[220:223], v210 offset:23104
	s_waitcnt lgkmcnt(5)
	v_mfma_f32_32x32x16_bf16 v[32:47], v[228:231], v[244:247], v[32:47]
	s_waitcnt lgkmcnt(4)
	v_mfma_f32_32x32x16_bf16 v[48:63], v[228:231], v[252:255], v[48:63]
	ds_read_b128 v[228:231], v96 offset:59968
	s_waitcnt lgkmcnt(4)
	v_mfma_f32_32x32x16_bf16 v[16:31], v[212:215], v[244:247], v[16:31]
	ds_read_b128 v[244:247], v96 offset:55392
	v_mfma_f32_32x32x16_bf16 v[0:15], v[212:215], v[252:255], v[0:15]
	ds_read_b128 v[212:215], v210 offset:18528
	ds_read_b128 v[252:255], v210 offset:23136
	s_waitcnt lgkmcnt(5)
	v_mfma_f32_32x32x16_bf16 v[32:47], v[216:219], v[224:227], v[32:47]
	s_waitcnt vmcnt(15)
	ds_write_b128 v209, v[64:67]
	global_load_dwordx4 v[64:67], v[148:149], off offset:1280
	s_waitcnt lgkmcnt(5)
	v_mfma_f32_32x32x16_bf16 v[48:63], v[216:219], v[220:223], v[48:63]
	ds_read_b128 v[216:219], v96 offset:60000
	s_waitcnt vmcnt(15)
	ds_write_b128 v209, v[72:75] offset:4608
	global_load_dwordx4 v[72:75], v[150:151], off offset:1280
	s_waitcnt lgkmcnt(6)
	v_mfma_f32_32x32x16_bf16 v[16:31], v[228:231], v[224:227], v[16:31]
	s_waitcnt vmcnt(15)
	ds_write_b128 v209, v[76:79] offset:9216
	global_load_dwordx4 v[76:79], v[152:153], off offset:1280
	v_mfma_f32_32x32x16_bf16 v[0:15], v[228:231], v[220:223], v[0:15]
	s_waitcnt vmcnt(15)
	ds_write_b128 v209, v[80:83] offset:13824
	global_load_dwordx4 v[80:83], v[154:155], off offset:1280
	s_waitcnt lgkmcnt(6)
	v_mfma_f32_32x32x16_bf16 v[32:47], v[244:247], v[212:215], v[32:47]
	s_waitcnt vmcnt(15)
	ds_write_b128 v209, v[102:105] offset:36864
	global_load_dwordx4 v[102:105], v[146:147], off offset:1280
	s_waitcnt lgkmcnt(6)
	v_mfma_f32_32x32x16_bf16 v[48:63], v[244:247], v[252:255], v[48:63]
	s_waitcnt vmcnt(15)
	ds_write_b128 v209, v[118:121] offset:41472
	global_load_dwordx4 v[118:121], v[156:157], off offset:1280
	s_waitcnt lgkmcnt(5)
	v_mfma_f32_32x32x16_bf16 v[16:31], v[216:219], v[212:215], v[16:31]
	s_waitcnt vmcnt(15)
	ds_write_b128 v209, v[122:125] offset:46080
	global_load_dwordx4 v[122:125], v[158:159], off offset:1280
	v_mfma_f32_32x32x16_bf16 v[0:15], v[216:219], v[252:255], v[0:15]
	s_waitcnt vmcnt(15)
	ds_write_b128 v209, v[126:129] offset:50688
	global_load_dwordx4 v[126:129], v[160:161], off offset:1280
	s_setprio 0
	s_waitcnt lgkmcnt(0)
	s_barrier
	s_setprio 1
	ds_read_b128 v[212:215], v96 offset:36864
	ds_read_b128 v[216:219], v210
	ds_read_b128 v[220:223], v210 offset:4608
	ds_read_b128 v[224:227], v96 offset:41472
	ds_read_b128 v[228:231], v96 offset:36896
	ds_read_b128 v[244:247], v210 offset:32
	ds_read_b128 v[252:255], v210 offset:4640
	s_waitcnt lgkmcnt(5)
	v_mfma_f32_32x32x16_bf16 v[32:47], v[212:215], v[216:219], v[32:47]
	s_waitcnt lgkmcnt(4)
	v_mfma_f32_32x32x16_bf16 v[48:63], v[212:215], v[220:223], v[48:63]
	ds_read_b128 v[212:215], v96 offset:41504
	s_waitcnt lgkmcnt(4)
	v_mfma_f32_32x32x16_bf16 v[16:31], v[224:227], v[216:219], v[16:31]
	ds_read_b128 v[216:219], v96 offset:36928
	v_mfma_f32_32x32x16_bf16 v[0:15], v[224:227], v[220:223], v[0:15]
	ds_read_b128 v[224:227], v210 offset:64
	ds_read_b128 v[220:223], v210 offset:4672
	s_waitcnt lgkmcnt(5)
	v_mfma_f32_32x32x16_bf16 v[32:47], v[228:231], v[244:247], v[32:47]
	s_waitcnt lgkmcnt(4)
	v_mfma_f32_32x32x16_bf16 v[48:63], v[228:231], v[252:255], v[48:63]
	ds_read_b128 v[228:231], v96 offset:41536
	s_waitcnt lgkmcnt(4)
	v_mfma_f32_32x32x16_bf16 v[16:31], v[212:215], v[244:247], v[16:31]
	ds_read_b128 v[244:247], v96 offset:36960
	v_mfma_f32_32x32x16_bf16 v[0:15], v[212:215], v[252:255], v[0:15]
	ds_read_b128 v[212:215], v210 offset:96
	ds_read_b128 v[252:255], v210 offset:4704
	s_waitcnt lgkmcnt(5)
	v_mfma_f32_32x32x16_bf16 v[32:47], v[216:219], v[224:227], v[32:47]
	s_waitcnt vmcnt(15)
	ds_write_b128 v209, v[68:71] offset:18432
	global_load_dwordx4 v[68:71], v[148:149], off offset:1408
	s_waitcnt lgkmcnt(5)
	v_mfma_f32_32x32x16_bf16 v[48:63], v[216:219], v[220:223], v[48:63]
	ds_read_b128 v[216:219], v96 offset:41568
	s_waitcnt vmcnt(15)
	ds_write_b128 v209, v[84:87] offset:23040
	global_load_dwordx4 v[84:87], v[150:151], off offset:1408
	s_waitcnt lgkmcnt(6)
	v_mfma_f32_32x32x16_bf16 v[16:31], v[228:231], v[224:227], v[16:31]
	s_waitcnt vmcnt(15)
	ds_write_b128 v209, v[88:91] offset:27648
	global_load_dwordx4 v[88:91], v[152:153], off offset:1408
	v_mfma_f32_32x32x16_bf16 v[0:15], v[228:231], v[220:223], v[0:15]
	s_waitcnt vmcnt(15)
	ds_write_b128 v209, v[92:95] offset:32256
	global_load_dwordx4 v[92:95], v[154:155], off offset:1408
	s_waitcnt lgkmcnt(6)
	v_mfma_f32_32x32x16_bf16 v[32:47], v[244:247], v[212:215], v[32:47]
	s_waitcnt vmcnt(15)
	ds_write_b128 v209, v[98:101] offset:55296
	global_load_dwordx4 v[98:101], v[146:147], off offset:1408
	s_waitcnt lgkmcnt(6)
	v_mfma_f32_32x32x16_bf16 v[48:63], v[244:247], v[252:255], v[48:63]
	s_waitcnt vmcnt(15)
	ds_write_b128 v209, v[106:109] offset:59904
	global_load_dwordx4 v[106:109], v[156:157], off offset:1408
	s_waitcnt lgkmcnt(5)
	v_mfma_f32_32x32x16_bf16 v[16:31], v[216:219], v[212:215], v[16:31]
	s_waitcnt vmcnt(15)
	ds_write_b128 v209, v[110:113] offset:64512
	global_load_dwordx4 v[110:113], v[158:159], off offset:1408
	v_mfma_f32_32x32x16_bf16 v[0:15], v[216:219], v[252:255], v[0:15]
	s_waitcnt vmcnt(15)
	ds_write_b128 v211, v[114:117] offset:13824
	global_load_dwordx4 v[114:117], v[160:161], off offset:1408
	s_setprio 0
	s_waitcnt lgkmcnt(0)
	s_barrier
	s_setprio 1
	ds_read_b128 v[212:215], v96 offset:55296
	ds_read_b128 v[216:219], v210 offset:18432
	ds_read_b128 v[220:223], v210 offset:23040
	ds_read_b128 v[224:227], v96 offset:59904
	ds_read_b128 v[228:231], v96 offset:55328
	ds_read_b128 v[244:247], v210 offset:18464
	ds_read_b128 v[252:255], v210 offset:23072
	s_waitcnt lgkmcnt(5)
	v_mfma_f32_32x32x16_bf16 v[32:47], v[212:215], v[216:219], v[32:47]
	s_waitcnt lgkmcnt(4)
	v_mfma_f32_32x32x16_bf16 v[48:63], v[212:215], v[220:223], v[48:63]
	ds_read_b128 v[212:215], v96 offset:59936
	s_waitcnt lgkmcnt(4)
	v_mfma_f32_32x32x16_bf16 v[16:31], v[224:227], v[216:219], v[16:31]
	ds_read_b128 v[216:219], v96 offset:55360
	v_mfma_f32_32x32x16_bf16 v[0:15], v[224:227], v[220:223], v[0:15]
	ds_read_b128 v[224:227], v210 offset:18496
	ds_read_b128 v[220:223], v210 offset:23104
	s_waitcnt lgkmcnt(5)
	v_mfma_f32_32x32x16_bf16 v[32:47], v[228:231], v[244:247], v[32:47]
	s_waitcnt lgkmcnt(4)
	v_mfma_f32_32x32x16_bf16 v[48:63], v[228:231], v[252:255], v[48:63]
	ds_read_b128 v[228:231], v96 offset:59968
	s_waitcnt lgkmcnt(4)
	v_mfma_f32_32x32x16_bf16 v[16:31], v[212:215], v[244:247], v[16:31]
	ds_read_b128 v[244:247], v96 offset:55392
	v_mfma_f32_32x32x16_bf16 v[0:15], v[212:215], v[252:255], v[0:15]
	ds_read_b128 v[212:215], v210 offset:18528
	ds_read_b128 v[252:255], v210 offset:23136
	s_waitcnt lgkmcnt(5)
	v_mfma_f32_32x32x16_bf16 v[32:47], v[216:219], v[224:227], v[32:47]
	s_waitcnt vmcnt(15)
	ds_write_b128 v209, v[64:67]
	global_load_dwordx4 v[64:67], v[148:149], off offset:1536
	s_waitcnt lgkmcnt(5)
	v_mfma_f32_32x32x16_bf16 v[48:63], v[216:219], v[220:223], v[48:63]
	ds_read_b128 v[216:219], v96 offset:60000
	s_waitcnt vmcnt(15)
	ds_write_b128 v209, v[72:75] offset:4608
	global_load_dwordx4 v[72:75], v[150:151], off offset:1536
	s_waitcnt lgkmcnt(6)
	v_mfma_f32_32x32x16_bf16 v[16:31], v[228:231], v[224:227], v[16:31]
	s_waitcnt vmcnt(15)
	ds_write_b128 v209, v[76:79] offset:9216
	global_load_dwordx4 v[76:79], v[152:153], off offset:1536
	v_mfma_f32_32x32x16_bf16 v[0:15], v[228:231], v[220:223], v[0:15]
	s_waitcnt vmcnt(15)
	ds_write_b128 v209, v[80:83] offset:13824
	global_load_dwordx4 v[80:83], v[154:155], off offset:1536
	s_waitcnt lgkmcnt(6)
	v_mfma_f32_32x32x16_bf16 v[32:47], v[244:247], v[212:215], v[32:47]
	s_waitcnt vmcnt(15)
	ds_write_b128 v209, v[102:105] offset:36864
	global_load_dwordx4 v[102:105], v[146:147], off offset:1536
	s_waitcnt lgkmcnt(6)
	v_mfma_f32_32x32x16_bf16 v[48:63], v[244:247], v[252:255], v[48:63]
	s_waitcnt vmcnt(15)
	ds_write_b128 v209, v[118:121] offset:41472
	global_load_dwordx4 v[118:121], v[156:157], off offset:1536
	s_waitcnt lgkmcnt(5)
	v_mfma_f32_32x32x16_bf16 v[16:31], v[216:219], v[212:215], v[16:31]
	s_waitcnt vmcnt(15)
	ds_write_b128 v209, v[122:125] offset:46080
	global_load_dwordx4 v[122:125], v[158:159], off offset:1536
	v_mfma_f32_32x32x16_bf16 v[0:15], v[216:219], v[252:255], v[0:15]
	s_waitcnt vmcnt(15)
	ds_write_b128 v209, v[126:129] offset:50688
	global_load_dwordx4 v[126:129], v[160:161], off offset:1536
	s_setprio 0
	s_waitcnt lgkmcnt(0)
	s_barrier
	s_setprio 1
	ds_read_b128 v[212:215], v96 offset:36864
	ds_read_b128 v[216:219], v210
	ds_read_b128 v[220:223], v210 offset:4608
	ds_read_b128 v[224:227], v96 offset:41472
	ds_read_b128 v[228:231], v96 offset:36896
	ds_read_b128 v[244:247], v210 offset:32
	ds_read_b128 v[252:255], v210 offset:4640
	s_waitcnt lgkmcnt(5)
	v_mfma_f32_32x32x16_bf16 v[32:47], v[212:215], v[216:219], v[32:47]
	s_waitcnt lgkmcnt(4)
	v_mfma_f32_32x32x16_bf16 v[48:63], v[212:215], v[220:223], v[48:63]
	ds_read_b128 v[212:215], v96 offset:41504
	s_waitcnt lgkmcnt(4)
	v_mfma_f32_32x32x16_bf16 v[16:31], v[224:227], v[216:219], v[16:31]
	ds_read_b128 v[216:219], v96 offset:36928
	v_mfma_f32_32x32x16_bf16 v[0:15], v[224:227], v[220:223], v[0:15]
	ds_read_b128 v[224:227], v210 offset:64
	ds_read_b128 v[220:223], v210 offset:4672
	s_waitcnt lgkmcnt(5)
	v_mfma_f32_32x32x16_bf16 v[32:47], v[228:231], v[244:247], v[32:47]
	s_waitcnt lgkmcnt(4)
	v_mfma_f32_32x32x16_bf16 v[48:63], v[228:231], v[252:255], v[48:63]
	ds_read_b128 v[228:231], v96 offset:41536
	s_waitcnt lgkmcnt(4)
	v_mfma_f32_32x32x16_bf16 v[16:31], v[212:215], v[244:247], v[16:31]
	ds_read_b128 v[244:247], v96 offset:36960
	v_mfma_f32_32x32x16_bf16 v[0:15], v[212:215], v[252:255], v[0:15]
	ds_read_b128 v[212:215], v210 offset:96
	ds_read_b128 v[252:255], v210 offset:4704
	s_waitcnt lgkmcnt(5)
	v_mfma_f32_32x32x16_bf16 v[32:47], v[216:219], v[224:227], v[32:47]
	s_waitcnt vmcnt(15)
	ds_write_b128 v209, v[68:71] offset:18432
	global_load_dwordx4 v[68:71], v[148:149], off offset:1664
	s_waitcnt lgkmcnt(5)
	v_mfma_f32_32x32x16_bf16 v[48:63], v[216:219], v[220:223], v[48:63]
	ds_read_b128 v[216:219], v96 offset:41568
	s_waitcnt vmcnt(15)
	ds_write_b128 v209, v[84:87] offset:23040
	global_load_dwordx4 v[84:87], v[150:151], off offset:1664
	s_waitcnt lgkmcnt(6)
	v_mfma_f32_32x32x16_bf16 v[16:31], v[228:231], v[224:227], v[16:31]
	s_waitcnt vmcnt(15)
	ds_write_b128 v209, v[88:91] offset:27648
	global_load_dwordx4 v[88:91], v[152:153], off offset:1664
	v_mfma_f32_32x32x16_bf16 v[0:15], v[228:231], v[220:223], v[0:15]
	s_waitcnt vmcnt(15)
	ds_write_b128 v209, v[92:95] offset:32256
	global_load_dwordx4 v[92:95], v[154:155], off offset:1664
	s_waitcnt lgkmcnt(6)
	v_mfma_f32_32x32x16_bf16 v[32:47], v[244:247], v[212:215], v[32:47]
	s_waitcnt vmcnt(15)
	ds_write_b128 v209, v[98:101] offset:55296
	global_load_dwordx4 v[98:101], v[146:147], off offset:1664
	s_waitcnt lgkmcnt(6)
	v_mfma_f32_32x32x16_bf16 v[48:63], v[244:247], v[252:255], v[48:63]
	s_waitcnt vmcnt(15)
	ds_write_b128 v209, v[106:109] offset:59904
	global_load_dwordx4 v[106:109], v[156:157], off offset:1664
	s_waitcnt lgkmcnt(5)
	v_mfma_f32_32x32x16_bf16 v[16:31], v[216:219], v[212:215], v[16:31]
	s_waitcnt vmcnt(15)
	ds_write_b128 v209, v[110:113] offset:64512
	global_load_dwordx4 v[110:113], v[158:159], off offset:1664
	v_mfma_f32_32x32x16_bf16 v[0:15], v[216:219], v[252:255], v[0:15]
	s_waitcnt vmcnt(15)
	ds_write_b128 v211, v[114:117] offset:13824
	global_load_dwordx4 v[114:117], v[160:161], off offset:1664
	s_setprio 0
	s_waitcnt lgkmcnt(0)
	s_barrier
	s_setprio 1
	ds_read_b128 v[212:215], v96 offset:55296
	ds_read_b128 v[216:219], v210 offset:18432
	ds_read_b128 v[220:223], v210 offset:23040
	ds_read_b128 v[224:227], v96 offset:59904
	ds_read_b128 v[228:231], v96 offset:55328
	ds_read_b128 v[244:247], v210 offset:18464
	ds_read_b128 v[252:255], v210 offset:23072
	s_waitcnt lgkmcnt(5)
	v_mfma_f32_32x32x16_bf16 v[32:47], v[212:215], v[216:219], v[32:47]
	s_waitcnt lgkmcnt(4)
	v_mfma_f32_32x32x16_bf16 v[48:63], v[212:215], v[220:223], v[48:63]
	ds_read_b128 v[212:215], v96 offset:59936
	s_waitcnt lgkmcnt(4)
	v_mfma_f32_32x32x16_bf16 v[16:31], v[224:227], v[216:219], v[16:31]
	ds_read_b128 v[216:219], v96 offset:55360
	v_mfma_f32_32x32x16_bf16 v[0:15], v[224:227], v[220:223], v[0:15]
	ds_read_b128 v[224:227], v210 offset:18496
	ds_read_b128 v[220:223], v210 offset:23104
	s_waitcnt lgkmcnt(5)
	v_mfma_f32_32x32x16_bf16 v[32:47], v[228:231], v[244:247], v[32:47]
	s_waitcnt lgkmcnt(4)
	v_mfma_f32_32x32x16_bf16 v[48:63], v[228:231], v[252:255], v[48:63]
	ds_read_b128 v[228:231], v96 offset:59968
	s_waitcnt lgkmcnt(4)
	v_mfma_f32_32x32x16_bf16 v[16:31], v[212:215], v[244:247], v[16:31]
	ds_read_b128 v[244:247], v96 offset:55392
	v_mfma_f32_32x32x16_bf16 v[0:15], v[212:215], v[252:255], v[0:15]
	ds_read_b128 v[212:215], v210 offset:18528
	ds_read_b128 v[252:255], v210 offset:23136
	s_waitcnt lgkmcnt(5)
	v_mfma_f32_32x32x16_bf16 v[32:47], v[216:219], v[224:227], v[32:47]
	s_waitcnt vmcnt(15)
	ds_write_b128 v209, v[64:67]
	global_load_dwordx4 v[64:67], v[148:149], off offset:1792
	s_waitcnt lgkmcnt(5)
	v_mfma_f32_32x32x16_bf16 v[48:63], v[216:219], v[220:223], v[48:63]
	ds_read_b128 v[216:219], v96 offset:60000
	s_waitcnt vmcnt(15)
	ds_write_b128 v209, v[72:75] offset:4608
	global_load_dwordx4 v[72:75], v[150:151], off offset:1792
	s_waitcnt lgkmcnt(6)
	v_mfma_f32_32x32x16_bf16 v[16:31], v[228:231], v[224:227], v[16:31]
	s_waitcnt vmcnt(15)
	ds_write_b128 v209, v[76:79] offset:9216
	global_load_dwordx4 v[76:79], v[152:153], off offset:1792
	v_mfma_f32_32x32x16_bf16 v[0:15], v[228:231], v[220:223], v[0:15]
	s_waitcnt vmcnt(15)
	ds_write_b128 v209, v[80:83] offset:13824
	global_load_dwordx4 v[80:83], v[154:155], off offset:1792
	s_waitcnt lgkmcnt(6)
	v_mfma_f32_32x32x16_bf16 v[32:47], v[244:247], v[212:215], v[32:47]
	s_waitcnt vmcnt(15)
	ds_write_b128 v209, v[102:105] offset:36864
	global_load_dwordx4 v[102:105], v[146:147], off offset:1792
	s_waitcnt lgkmcnt(6)
	v_mfma_f32_32x32x16_bf16 v[48:63], v[244:247], v[252:255], v[48:63]
	s_waitcnt vmcnt(15)
	ds_write_b128 v209, v[118:121] offset:41472
	global_load_dwordx4 v[118:121], v[156:157], off offset:1792
	s_waitcnt lgkmcnt(5)
	v_mfma_f32_32x32x16_bf16 v[16:31], v[216:219], v[212:215], v[16:31]
	s_waitcnt vmcnt(15)
	ds_write_b128 v209, v[122:125] offset:46080
	global_load_dwordx4 v[122:125], v[158:159], off offset:1792
	v_mfma_f32_32x32x16_bf16 v[0:15], v[216:219], v[252:255], v[0:15]
	s_waitcnt vmcnt(15)
	ds_write_b128 v209, v[126:129] offset:50688
	global_load_dwordx4 v[126:129], v[160:161], off offset:1792
	s_setprio 0
	s_waitcnt lgkmcnt(0)
	s_barrier
	s_setprio 1
	ds_read_b128 v[212:215], v96 offset:36864
	ds_read_b128 v[216:219], v210
	ds_read_b128 v[220:223], v210 offset:4608
	ds_read_b128 v[224:227], v96 offset:41472
	ds_read_b128 v[228:231], v96 offset:36896
	ds_read_b128 v[244:247], v210 offset:32
	ds_read_b128 v[252:255], v210 offset:4640
	s_waitcnt lgkmcnt(5)
	v_mfma_f32_32x32x16_bf16 v[32:47], v[212:215], v[216:219], v[32:47]
	s_waitcnt lgkmcnt(4)
	v_mfma_f32_32x32x16_bf16 v[48:63], v[212:215], v[220:223], v[48:63]
	ds_read_b128 v[212:215], v96 offset:41504
	s_waitcnt lgkmcnt(4)
	v_mfma_f32_32x32x16_bf16 v[16:31], v[224:227], v[216:219], v[16:31]
	ds_read_b128 v[216:219], v96 offset:36928
	v_mfma_f32_32x32x16_bf16 v[0:15], v[224:227], v[220:223], v[0:15]
	ds_read_b128 v[224:227], v210 offset:64
	ds_read_b128 v[220:223], v210 offset:4672
	s_waitcnt lgkmcnt(5)
	v_mfma_f32_32x32x16_bf16 v[32:47], v[228:231], v[244:247], v[32:47]
	s_waitcnt lgkmcnt(4)
	v_mfma_f32_32x32x16_bf16 v[48:63], v[228:231], v[252:255], v[48:63]
	ds_read_b128 v[228:231], v96 offset:41536
	s_waitcnt lgkmcnt(4)
	v_mfma_f32_32x32x16_bf16 v[16:31], v[212:215], v[244:247], v[16:31]
	ds_read_b128 v[244:247], v96 offset:36960
	v_mfma_f32_32x32x16_bf16 v[0:15], v[212:215], v[252:255], v[0:15]
	ds_read_b128 v[212:215], v210 offset:96
	ds_read_b128 v[252:255], v210 offset:4704
	s_waitcnt lgkmcnt(5)
	v_mfma_f32_32x32x16_bf16 v[32:47], v[216:219], v[224:227], v[32:47]
	s_waitcnt vmcnt(15)
	ds_write_b128 v209, v[68:71] offset:18432
	global_load_dwordx4 v[68:71], v[148:149], off offset:1920
	s_waitcnt lgkmcnt(5)
	v_mfma_f32_32x32x16_bf16 v[48:63], v[216:219], v[220:223], v[48:63]
	ds_read_b128 v[216:219], v96 offset:41568
	s_waitcnt vmcnt(15)
	ds_write_b128 v209, v[84:87] offset:23040
	global_load_dwordx4 v[84:87], v[150:151], off offset:1920
	s_waitcnt lgkmcnt(6)
	v_mfma_f32_32x32x16_bf16 v[16:31], v[228:231], v[224:227], v[16:31]
	s_waitcnt vmcnt(15)
	ds_write_b128 v209, v[88:91] offset:27648
	global_load_dwordx4 v[88:91], v[152:153], off offset:1920
	v_mfma_f32_32x32x16_bf16 v[0:15], v[228:231], v[220:223], v[0:15]
	s_waitcnt vmcnt(15)
	ds_write_b128 v209, v[92:95] offset:32256
	global_load_dwordx4 v[92:95], v[154:155], off offset:1920
	s_waitcnt lgkmcnt(6)
	v_mfma_f32_32x32x16_bf16 v[32:47], v[244:247], v[212:215], v[32:47]
	s_waitcnt vmcnt(15)
	ds_write_b128 v209, v[98:101] offset:55296
	global_load_dwordx4 v[98:101], v[146:147], off offset:1920
	s_waitcnt lgkmcnt(6)
	v_mfma_f32_32x32x16_bf16 v[48:63], v[244:247], v[252:255], v[48:63]
	s_waitcnt vmcnt(15)
	ds_write_b128 v209, v[106:109] offset:59904
	global_load_dwordx4 v[106:109], v[156:157], off offset:1920
	s_waitcnt lgkmcnt(5)
	v_mfma_f32_32x32x16_bf16 v[16:31], v[216:219], v[212:215], v[16:31]
	s_waitcnt vmcnt(15)
	ds_write_b128 v209, v[110:113] offset:64512
	global_load_dwordx4 v[110:113], v[158:159], off offset:1920
	v_mfma_f32_32x32x16_bf16 v[0:15], v[216:219], v[252:255], v[0:15]
	s_waitcnt vmcnt(15)
	ds_write_b128 v211, v[114:117] offset:13824
	global_load_dwordx4 v[114:117], v[160:161], off offset:1920
	s_setprio 0
	s_waitcnt lgkmcnt(0)
	s_barrier
	s_setprio 1
	ds_read_b128 v[212:215], v96 offset:55296
	ds_read_b128 v[216:219], v210 offset:18432
	ds_read_b128 v[220:223], v210 offset:23040
	ds_read_b128 v[224:227], v96 offset:59904
	ds_read_b128 v[228:231], v96 offset:55328
	ds_read_b128 v[244:247], v210 offset:18464
	ds_read_b128 v[252:255], v210 offset:23072
	s_waitcnt lgkmcnt(5)
	v_mfma_f32_32x32x16_bf16 v[32:47], v[212:215], v[216:219], v[32:47]
	s_waitcnt lgkmcnt(4)
	v_mfma_f32_32x32x16_bf16 v[48:63], v[212:215], v[220:223], v[48:63]
	ds_read_b128 v[212:215], v96 offset:59936
	s_waitcnt lgkmcnt(4)
	v_mfma_f32_32x32x16_bf16 v[16:31], v[224:227], v[216:219], v[16:31]
	ds_read_b128 v[216:219], v96 offset:55360
	v_mfma_f32_32x32x16_bf16 v[0:15], v[224:227], v[220:223], v[0:15]
	ds_read_b128 v[224:227], v210 offset:18496
	ds_read_b128 v[220:223], v210 offset:23104
	s_waitcnt lgkmcnt(5)
	v_mfma_f32_32x32x16_bf16 v[32:47], v[228:231], v[244:247], v[32:47]
	s_waitcnt lgkmcnt(4)
	v_mfma_f32_32x32x16_bf16 v[48:63], v[228:231], v[252:255], v[48:63]
	ds_read_b128 v[228:231], v96 offset:59968
	s_waitcnt lgkmcnt(4)
	v_mfma_f32_32x32x16_bf16 v[16:31], v[212:215], v[244:247], v[16:31]
	ds_read_b128 v[244:247], v96 offset:55392
	v_mfma_f32_32x32x16_bf16 v[0:15], v[212:215], v[252:255], v[0:15]
	ds_read_b128 v[212:215], v210 offset:18528
	ds_read_b128 v[252:255], v210 offset:23136
	s_waitcnt lgkmcnt(5)
	v_mfma_f32_32x32x16_bf16 v[32:47], v[216:219], v[224:227], v[32:47]
	s_waitcnt vmcnt(15)
	ds_write_b128 v209, v[64:67]
	global_load_dwordx4 v[64:67], v[148:149], off offset:2048
	s_waitcnt lgkmcnt(5)
	v_mfma_f32_32x32x16_bf16 v[48:63], v[216:219], v[220:223], v[48:63]
	ds_read_b128 v[216:219], v96 offset:60000
	s_waitcnt vmcnt(15)
	ds_write_b128 v209, v[72:75] offset:4608
	global_load_dwordx4 v[72:75], v[150:151], off offset:2048
	s_waitcnt lgkmcnt(6)
	v_mfma_f32_32x32x16_bf16 v[16:31], v[228:231], v[224:227], v[16:31]
	s_waitcnt vmcnt(15)
	ds_write_b128 v209, v[76:79] offset:9216
	global_load_dwordx4 v[76:79], v[152:153], off offset:2048
	v_mfma_f32_32x32x16_bf16 v[0:15], v[228:231], v[220:223], v[0:15]
	s_waitcnt vmcnt(15)
	ds_write_b128 v209, v[80:83] offset:13824
	global_load_dwordx4 v[80:83], v[154:155], off offset:2048
	s_waitcnt lgkmcnt(6)
	v_mfma_f32_32x32x16_bf16 v[32:47], v[244:247], v[212:215], v[32:47]
	s_waitcnt vmcnt(15)
	ds_write_b128 v209, v[102:105] offset:36864
	global_load_dwordx4 v[102:105], v[146:147], off offset:2048
	s_waitcnt lgkmcnt(6)
	v_mfma_f32_32x32x16_bf16 v[48:63], v[244:247], v[252:255], v[48:63]
	s_waitcnt vmcnt(15)
	ds_write_b128 v209, v[118:121] offset:41472
	global_load_dwordx4 v[118:121], v[156:157], off offset:2048
	s_waitcnt lgkmcnt(5)
	v_mfma_f32_32x32x16_bf16 v[16:31], v[216:219], v[212:215], v[16:31]
	s_waitcnt vmcnt(15)
	ds_write_b128 v209, v[122:125] offset:46080
	global_load_dwordx4 v[122:125], v[158:159], off offset:2048
	v_mfma_f32_32x32x16_bf16 v[0:15], v[216:219], v[252:255], v[0:15]
	s_waitcnt vmcnt(15)
	ds_write_b128 v209, v[126:129] offset:50688
	global_load_dwordx4 v[126:129], v[160:161], off offset:2048
	s_setprio 0
	s_waitcnt lgkmcnt(0)
	s_barrier
	s_setprio 1
	ds_read_b128 v[212:215], v96 offset:36864
	ds_read_b128 v[216:219], v210
	ds_read_b128 v[220:223], v210 offset:4608
	ds_read_b128 v[224:227], v96 offset:41472
	ds_read_b128 v[228:231], v96 offset:36896
	ds_read_b128 v[244:247], v210 offset:32
	ds_read_b128 v[252:255], v210 offset:4640
	s_waitcnt lgkmcnt(5)
	v_mfma_f32_32x32x16_bf16 v[32:47], v[212:215], v[216:219], v[32:47]
	s_waitcnt lgkmcnt(4)
	v_mfma_f32_32x32x16_bf16 v[48:63], v[212:215], v[220:223], v[48:63]
	ds_read_b128 v[212:215], v96 offset:41504
	s_waitcnt lgkmcnt(4)
	v_mfma_f32_32x32x16_bf16 v[16:31], v[224:227], v[216:219], v[16:31]
	ds_read_b128 v[216:219], v96 offset:36928
	v_mfma_f32_32x32x16_bf16 v[0:15], v[224:227], v[220:223], v[0:15]
	ds_read_b128 v[224:227], v210 offset:64
	ds_read_b128 v[220:223], v210 offset:4672
	s_waitcnt lgkmcnt(5)
	v_mfma_f32_32x32x16_bf16 v[32:47], v[228:231], v[244:247], v[32:47]
	s_waitcnt lgkmcnt(4)
	v_mfma_f32_32x32x16_bf16 v[48:63], v[228:231], v[252:255], v[48:63]
	ds_read_b128 v[228:231], v96 offset:41536
	s_waitcnt lgkmcnt(4)
	v_mfma_f32_32x32x16_bf16 v[16:31], v[212:215], v[244:247], v[16:31]
	ds_read_b128 v[244:247], v96 offset:36960
	v_mfma_f32_32x32x16_bf16 v[0:15], v[212:215], v[252:255], v[0:15]
	ds_read_b128 v[212:215], v210 offset:96
	ds_read_b128 v[252:255], v210 offset:4704
	s_waitcnt lgkmcnt(5)
	v_mfma_f32_32x32x16_bf16 v[32:47], v[216:219], v[224:227], v[32:47]
	s_waitcnt vmcnt(15)
	ds_write_b128 v209, v[68:71] offset:18432
	global_load_dwordx4 v[68:71], v[148:149], off offset:2176
	s_waitcnt lgkmcnt(5)
	v_mfma_f32_32x32x16_bf16 v[48:63], v[216:219], v[220:223], v[48:63]
	ds_read_b128 v[216:219], v96 offset:41568
	s_waitcnt vmcnt(15)
	ds_write_b128 v209, v[84:87] offset:23040
	global_load_dwordx4 v[84:87], v[150:151], off offset:2176
	s_waitcnt lgkmcnt(6)
	v_mfma_f32_32x32x16_bf16 v[16:31], v[228:231], v[224:227], v[16:31]
	s_waitcnt vmcnt(15)
	ds_write_b128 v209, v[88:91] offset:27648
	global_load_dwordx4 v[88:91], v[152:153], off offset:2176
	v_mfma_f32_32x32x16_bf16 v[0:15], v[228:231], v[220:223], v[0:15]
	s_waitcnt vmcnt(15)
	ds_write_b128 v209, v[92:95] offset:32256
	global_load_dwordx4 v[92:95], v[154:155], off offset:2176
	s_waitcnt lgkmcnt(6)
	v_mfma_f32_32x32x16_bf16 v[32:47], v[244:247], v[212:215], v[32:47]
	s_waitcnt vmcnt(15)
	ds_write_b128 v209, v[98:101] offset:55296
	global_load_dwordx4 v[98:101], v[146:147], off offset:2176
	s_waitcnt lgkmcnt(6)
	v_mfma_f32_32x32x16_bf16 v[48:63], v[244:247], v[252:255], v[48:63]
	s_waitcnt vmcnt(15)
	ds_write_b128 v209, v[106:109] offset:59904
	global_load_dwordx4 v[106:109], v[156:157], off offset:2176
	s_waitcnt lgkmcnt(5)
	v_mfma_f32_32x32x16_bf16 v[16:31], v[216:219], v[212:215], v[16:31]
	s_waitcnt vmcnt(15)
	ds_write_b128 v209, v[110:113] offset:64512
	global_load_dwordx4 v[110:113], v[158:159], off offset:2176
	v_mfma_f32_32x32x16_bf16 v[0:15], v[216:219], v[252:255], v[0:15]
	s_waitcnt vmcnt(15)
	ds_write_b128 v211, v[114:117] offset:13824
	global_load_dwordx4 v[114:117], v[160:161], off offset:2176
	s_setprio 0
	s_waitcnt lgkmcnt(0)
	s_barrier
	s_setprio 1
	ds_read_b128 v[212:215], v96 offset:55296
	ds_read_b128 v[216:219], v210 offset:18432
	ds_read_b128 v[220:223], v210 offset:23040
	ds_read_b128 v[224:227], v96 offset:59904
	ds_read_b128 v[228:231], v96 offset:55328
	ds_read_b128 v[244:247], v210 offset:18464
	ds_read_b128 v[252:255], v210 offset:23072
	s_waitcnt lgkmcnt(5)
	v_mfma_f32_32x32x16_bf16 v[32:47], v[212:215], v[216:219], v[32:47]
	s_waitcnt lgkmcnt(4)
	v_mfma_f32_32x32x16_bf16 v[48:63], v[212:215], v[220:223], v[48:63]
	ds_read_b128 v[212:215], v96 offset:59936
	s_waitcnt lgkmcnt(4)
	v_mfma_f32_32x32x16_bf16 v[16:31], v[224:227], v[216:219], v[16:31]
	ds_read_b128 v[216:219], v96 offset:55360
	v_mfma_f32_32x32x16_bf16 v[0:15], v[224:227], v[220:223], v[0:15]
	ds_read_b128 v[224:227], v210 offset:18496
	ds_read_b128 v[220:223], v210 offset:23104
	s_waitcnt lgkmcnt(5)
	v_mfma_f32_32x32x16_bf16 v[32:47], v[228:231], v[244:247], v[32:47]
	s_waitcnt lgkmcnt(4)
	v_mfma_f32_32x32x16_bf16 v[48:63], v[228:231], v[252:255], v[48:63]
	ds_read_b128 v[228:231], v96 offset:59968
	s_waitcnt lgkmcnt(4)
	v_mfma_f32_32x32x16_bf16 v[16:31], v[212:215], v[244:247], v[16:31]
	ds_read_b128 v[244:247], v96 offset:55392
	v_mfma_f32_32x32x16_bf16 v[0:15], v[212:215], v[252:255], v[0:15]
	ds_read_b128 v[212:215], v210 offset:18528
	ds_read_b128 v[252:255], v210 offset:23136
	s_waitcnt lgkmcnt(5)
	v_mfma_f32_32x32x16_bf16 v[32:47], v[216:219], v[224:227], v[32:47]
	s_waitcnt vmcnt(15)
	ds_write_b128 v209, v[64:67]
	global_load_dwordx4 v[64:67], v[148:149], off offset:2304
	s_waitcnt lgkmcnt(5)
	v_mfma_f32_32x32x16_bf16 v[48:63], v[216:219], v[220:223], v[48:63]
	ds_read_b128 v[216:219], v96 offset:60000
	s_waitcnt vmcnt(15)
	ds_write_b128 v209, v[72:75] offset:4608
	global_load_dwordx4 v[72:75], v[150:151], off offset:2304
	s_waitcnt lgkmcnt(6)
	v_mfma_f32_32x32x16_bf16 v[16:31], v[228:231], v[224:227], v[16:31]
	s_waitcnt vmcnt(15)
	ds_write_b128 v209, v[76:79] offset:9216
	global_load_dwordx4 v[76:79], v[152:153], off offset:2304
	v_mfma_f32_32x32x16_bf16 v[0:15], v[228:231], v[220:223], v[0:15]
	s_waitcnt vmcnt(15)
	ds_write_b128 v209, v[80:83] offset:13824
	global_load_dwordx4 v[80:83], v[154:155], off offset:2304
	s_waitcnt lgkmcnt(6)
	v_mfma_f32_32x32x16_bf16 v[32:47], v[244:247], v[212:215], v[32:47]
	s_waitcnt vmcnt(15)
	ds_write_b128 v209, v[102:105] offset:36864
	global_load_dwordx4 v[102:105], v[146:147], off offset:2304
	s_waitcnt lgkmcnt(6)
	v_mfma_f32_32x32x16_bf16 v[48:63], v[244:247], v[252:255], v[48:63]
	s_waitcnt vmcnt(15)
	ds_write_b128 v209, v[118:121] offset:41472
	global_load_dwordx4 v[118:121], v[156:157], off offset:2304
	s_waitcnt lgkmcnt(5)
	v_mfma_f32_32x32x16_bf16 v[16:31], v[216:219], v[212:215], v[16:31]
	s_waitcnt vmcnt(15)
	ds_write_b128 v209, v[122:125] offset:46080
	global_load_dwordx4 v[122:125], v[158:159], off offset:2304
	v_mfma_f32_32x32x16_bf16 v[0:15], v[216:219], v[252:255], v[0:15]
	s_waitcnt vmcnt(15)
	ds_write_b128 v209, v[126:129] offset:50688
	global_load_dwordx4 v[126:129], v[160:161], off offset:2304
	s_setprio 0
	s_waitcnt lgkmcnt(0)
	s_barrier
	s_setprio 1
	ds_read_b128 v[212:215], v96 offset:36864
	ds_read_b128 v[216:219], v210
	ds_read_b128 v[220:223], v210 offset:4608
	ds_read_b128 v[224:227], v96 offset:41472
	ds_read_b128 v[228:231], v96 offset:36896
	ds_read_b128 v[244:247], v210 offset:32
	ds_read_b128 v[252:255], v210 offset:4640
	s_waitcnt lgkmcnt(5)
	v_mfma_f32_32x32x16_bf16 v[32:47], v[212:215], v[216:219], v[32:47]
	s_waitcnt lgkmcnt(4)
	v_mfma_f32_32x32x16_bf16 v[48:63], v[212:215], v[220:223], v[48:63]
	ds_read_b128 v[212:215], v96 offset:41504
	s_waitcnt lgkmcnt(4)
	v_mfma_f32_32x32x16_bf16 v[16:31], v[224:227], v[216:219], v[16:31]
	ds_read_b128 v[216:219], v96 offset:36928
	v_mfma_f32_32x32x16_bf16 v[0:15], v[224:227], v[220:223], v[0:15]
	ds_read_b128 v[224:227], v210 offset:64
	ds_read_b128 v[220:223], v210 offset:4672
	s_waitcnt lgkmcnt(5)
	v_mfma_f32_32x32x16_bf16 v[32:47], v[228:231], v[244:247], v[32:47]
	s_waitcnt lgkmcnt(4)
	v_mfma_f32_32x32x16_bf16 v[48:63], v[228:231], v[252:255], v[48:63]
	ds_read_b128 v[228:231], v96 offset:41536
	s_waitcnt lgkmcnt(4)
	v_mfma_f32_32x32x16_bf16 v[16:31], v[212:215], v[244:247], v[16:31]
	ds_read_b128 v[244:247], v96 offset:36960
	v_mfma_f32_32x32x16_bf16 v[0:15], v[212:215], v[252:255], v[0:15]
	ds_read_b128 v[212:215], v210 offset:96
	ds_read_b128 v[252:255], v210 offset:4704
	s_waitcnt lgkmcnt(5)
	v_mfma_f32_32x32x16_bf16 v[32:47], v[216:219], v[224:227], v[32:47]
	s_waitcnt vmcnt(15)
	ds_write_b128 v209, v[68:71] offset:18432
	global_load_dwordx4 v[68:71], v[148:149], off offset:2432
	s_waitcnt lgkmcnt(5)
	v_mfma_f32_32x32x16_bf16 v[48:63], v[216:219], v[220:223], v[48:63]
	ds_read_b128 v[216:219], v96 offset:41568
	s_waitcnt vmcnt(15)
	ds_write_b128 v209, v[84:87] offset:23040
	global_load_dwordx4 v[84:87], v[150:151], off offset:2432
	s_waitcnt lgkmcnt(6)
	v_mfma_f32_32x32x16_bf16 v[16:31], v[228:231], v[224:227], v[16:31]
	s_waitcnt vmcnt(15)
	ds_write_b128 v209, v[88:91] offset:27648
	global_load_dwordx4 v[88:91], v[152:153], off offset:2432
	v_mfma_f32_32x32x16_bf16 v[0:15], v[228:231], v[220:223], v[0:15]
	s_waitcnt vmcnt(15)
	ds_write_b128 v209, v[92:95] offset:32256
	global_load_dwordx4 v[92:95], v[154:155], off offset:2432
	s_waitcnt lgkmcnt(6)
	v_mfma_f32_32x32x16_bf16 v[32:47], v[244:247], v[212:215], v[32:47]
	s_waitcnt vmcnt(15)
	ds_write_b128 v209, v[98:101] offset:55296
	global_load_dwordx4 v[98:101], v[146:147], off offset:2432
	s_waitcnt lgkmcnt(6)
	v_mfma_f32_32x32x16_bf16 v[48:63], v[244:247], v[252:255], v[48:63]
	s_waitcnt vmcnt(15)
	ds_write_b128 v209, v[106:109] offset:59904
	global_load_dwordx4 v[106:109], v[156:157], off offset:2432
	s_waitcnt lgkmcnt(5)
	v_mfma_f32_32x32x16_bf16 v[16:31], v[216:219], v[212:215], v[16:31]
	s_waitcnt vmcnt(15)
	ds_write_b128 v209, v[110:113] offset:64512
	global_load_dwordx4 v[110:113], v[158:159], off offset:2432
	v_mfma_f32_32x32x16_bf16 v[0:15], v[216:219], v[252:255], v[0:15]
	s_waitcnt vmcnt(15)
	ds_write_b128 v211, v[114:117] offset:13824
	global_load_dwordx4 v[114:117], v[160:161], off offset:2432
	s_setprio 0
	s_waitcnt lgkmcnt(0)
	s_barrier
	s_setprio 1
	ds_read_b128 v[212:215], v96 offset:55296
	ds_read_b128 v[216:219], v210 offset:18432
	ds_read_b128 v[220:223], v210 offset:23040
	ds_read_b128 v[224:227], v96 offset:59904
	ds_read_b128 v[228:231], v96 offset:55328
	ds_read_b128 v[244:247], v210 offset:18464
	ds_read_b128 v[252:255], v210 offset:23072
	s_waitcnt lgkmcnt(5)
	v_mfma_f32_32x32x16_bf16 v[32:47], v[212:215], v[216:219], v[32:47]
	s_waitcnt lgkmcnt(4)
	v_mfma_f32_32x32x16_bf16 v[48:63], v[212:215], v[220:223], v[48:63]
	ds_read_b128 v[212:215], v96 offset:59936
	s_waitcnt lgkmcnt(4)
	v_mfma_f32_32x32x16_bf16 v[16:31], v[224:227], v[216:219], v[16:31]
	ds_read_b128 v[216:219], v96 offset:55360
	v_mfma_f32_32x32x16_bf16 v[0:15], v[224:227], v[220:223], v[0:15]
	ds_read_b128 v[224:227], v210 offset:18496
	ds_read_b128 v[220:223], v210 offset:23104
	s_waitcnt lgkmcnt(5)
	v_mfma_f32_32x32x16_bf16 v[32:47], v[228:231], v[244:247], v[32:47]
	s_waitcnt lgkmcnt(4)
	v_mfma_f32_32x32x16_bf16 v[48:63], v[228:231], v[252:255], v[48:63]
	ds_read_b128 v[228:231], v96 offset:59968
	s_waitcnt lgkmcnt(4)
	v_mfma_f32_32x32x16_bf16 v[16:31], v[212:215], v[244:247], v[16:31]
	ds_read_b128 v[244:247], v96 offset:55392
	v_mfma_f32_32x32x16_bf16 v[0:15], v[212:215], v[252:255], v[0:15]
	ds_read_b128 v[212:215], v210 offset:18528
	ds_read_b128 v[252:255], v210 offset:23136
	s_waitcnt lgkmcnt(5)
	v_mfma_f32_32x32x16_bf16 v[32:47], v[216:219], v[224:227], v[32:47]
	s_waitcnt vmcnt(15)
	ds_write_b128 v209, v[64:67]
	global_load_dwordx4 v[64:67], v[148:149], off offset:2560
	s_waitcnt lgkmcnt(5)
	v_mfma_f32_32x32x16_bf16 v[48:63], v[216:219], v[220:223], v[48:63]
	ds_read_b128 v[216:219], v96 offset:60000
	s_waitcnt vmcnt(15)
	ds_write_b128 v209, v[72:75] offset:4608
	global_load_dwordx4 v[72:75], v[150:151], off offset:2560
	s_waitcnt lgkmcnt(6)
	v_mfma_f32_32x32x16_bf16 v[16:31], v[228:231], v[224:227], v[16:31]
	s_waitcnt vmcnt(15)
	ds_write_b128 v209, v[76:79] offset:9216
	global_load_dwordx4 v[76:79], v[152:153], off offset:2560
	v_mfma_f32_32x32x16_bf16 v[0:15], v[228:231], v[220:223], v[0:15]
	s_waitcnt vmcnt(15)
	ds_write_b128 v209, v[80:83] offset:13824
	global_load_dwordx4 v[80:83], v[154:155], off offset:2560
	s_waitcnt lgkmcnt(6)
	v_mfma_f32_32x32x16_bf16 v[32:47], v[244:247], v[212:215], v[32:47]
	s_waitcnt vmcnt(15)
	ds_write_b128 v209, v[102:105] offset:36864
	global_load_dwordx4 v[102:105], v[146:147], off offset:2560
	s_waitcnt lgkmcnt(6)
	v_mfma_f32_32x32x16_bf16 v[48:63], v[244:247], v[252:255], v[48:63]
	s_waitcnt vmcnt(15)
	ds_write_b128 v209, v[118:121] offset:41472
	global_load_dwordx4 v[118:121], v[156:157], off offset:2560
	s_waitcnt lgkmcnt(5)
	v_mfma_f32_32x32x16_bf16 v[16:31], v[216:219], v[212:215], v[16:31]
	s_waitcnt vmcnt(15)
	ds_write_b128 v209, v[122:125] offset:46080
	global_load_dwordx4 v[122:125], v[158:159], off offset:2560
	v_mfma_f32_32x32x16_bf16 v[0:15], v[216:219], v[252:255], v[0:15]
	s_waitcnt vmcnt(15)
	ds_write_b128 v209, v[126:129] offset:50688
	global_load_dwordx4 v[126:129], v[160:161], off offset:2560
	s_setprio 0
	s_waitcnt lgkmcnt(0)
	s_barrier
	s_setprio 1
	ds_read_b128 v[212:215], v96 offset:36864
	ds_read_b128 v[216:219], v210
	ds_read_b128 v[220:223], v210 offset:4608
	ds_read_b128 v[224:227], v96 offset:41472
	ds_read_b128 v[228:231], v96 offset:36896
	ds_read_b128 v[244:247], v210 offset:32
	ds_read_b128 v[252:255], v210 offset:4640
	s_waitcnt lgkmcnt(5)
	v_mfma_f32_32x32x16_bf16 v[32:47], v[212:215], v[216:219], v[32:47]
	s_waitcnt lgkmcnt(4)
	v_mfma_f32_32x32x16_bf16 v[48:63], v[212:215], v[220:223], v[48:63]
	ds_read_b128 v[212:215], v96 offset:41504
	s_waitcnt lgkmcnt(4)
	v_mfma_f32_32x32x16_bf16 v[16:31], v[224:227], v[216:219], v[16:31]
	ds_read_b128 v[216:219], v96 offset:36928
	v_mfma_f32_32x32x16_bf16 v[0:15], v[224:227], v[220:223], v[0:15]
	ds_read_b128 v[224:227], v210 offset:64
	ds_read_b128 v[220:223], v210 offset:4672
	s_waitcnt lgkmcnt(5)
	v_mfma_f32_32x32x16_bf16 v[32:47], v[228:231], v[244:247], v[32:47]
	s_waitcnt lgkmcnt(4)
	v_mfma_f32_32x32x16_bf16 v[48:63], v[228:231], v[252:255], v[48:63]
	ds_read_b128 v[228:231], v96 offset:41536
	s_waitcnt lgkmcnt(4)
	v_mfma_f32_32x32x16_bf16 v[16:31], v[212:215], v[244:247], v[16:31]
	ds_read_b128 v[244:247], v96 offset:36960
	v_mfma_f32_32x32x16_bf16 v[0:15], v[212:215], v[252:255], v[0:15]
	ds_read_b128 v[212:215], v210 offset:96
	ds_read_b128 v[252:255], v210 offset:4704
	s_waitcnt lgkmcnt(5)
	v_mfma_f32_32x32x16_bf16 v[32:47], v[216:219], v[224:227], v[32:47]
	s_waitcnt vmcnt(15)
	ds_write_b128 v209, v[68:71] offset:18432
	global_load_dwordx4 v[68:71], v[148:149], off offset:2688
	s_waitcnt lgkmcnt(5)
	v_mfma_f32_32x32x16_bf16 v[48:63], v[216:219], v[220:223], v[48:63]
	ds_read_b128 v[216:219], v96 offset:41568
	s_waitcnt vmcnt(15)
	ds_write_b128 v209, v[84:87] offset:23040
	global_load_dwordx4 v[84:87], v[150:151], off offset:2688
	s_waitcnt lgkmcnt(6)
	v_mfma_f32_32x32x16_bf16 v[16:31], v[228:231], v[224:227], v[16:31]
	s_waitcnt vmcnt(15)
	ds_write_b128 v209, v[88:91] offset:27648
	global_load_dwordx4 v[88:91], v[152:153], off offset:2688
	v_mfma_f32_32x32x16_bf16 v[0:15], v[228:231], v[220:223], v[0:15]
	s_waitcnt vmcnt(15)
	ds_write_b128 v209, v[92:95] offset:32256
	global_load_dwordx4 v[92:95], v[154:155], off offset:2688
	s_waitcnt lgkmcnt(6)
	v_mfma_f32_32x32x16_bf16 v[32:47], v[244:247], v[212:215], v[32:47]
	s_waitcnt vmcnt(15)
	ds_write_b128 v209, v[98:101] offset:55296
	global_load_dwordx4 v[98:101], v[146:147], off offset:2688
	s_waitcnt lgkmcnt(6)
	v_mfma_f32_32x32x16_bf16 v[48:63], v[244:247], v[252:255], v[48:63]
	s_waitcnt vmcnt(15)
	ds_write_b128 v209, v[106:109] offset:59904
	global_load_dwordx4 v[106:109], v[156:157], off offset:2688
	s_waitcnt lgkmcnt(5)
	v_mfma_f32_32x32x16_bf16 v[16:31], v[216:219], v[212:215], v[16:31]
	s_waitcnt vmcnt(15)
	ds_write_b128 v209, v[110:113] offset:64512
	global_load_dwordx4 v[110:113], v[158:159], off offset:2688
	v_mfma_f32_32x32x16_bf16 v[0:15], v[216:219], v[252:255], v[0:15]
	s_waitcnt vmcnt(15)
	ds_write_b128 v211, v[114:117] offset:13824
	global_load_dwordx4 v[114:117], v[160:161], off offset:2688
	s_setprio 0
	s_waitcnt lgkmcnt(0)
	s_barrier
	s_setprio 1
	ds_read_b128 v[212:215], v96 offset:55296
	ds_read_b128 v[216:219], v210 offset:18432
	ds_read_b128 v[220:223], v210 offset:23040
	ds_read_b128 v[224:227], v96 offset:59904
	ds_read_b128 v[228:231], v96 offset:55328
	ds_read_b128 v[244:247], v210 offset:18464
	ds_read_b128 v[252:255], v210 offset:23072
	s_waitcnt lgkmcnt(5)
	v_mfma_f32_32x32x16_bf16 v[32:47], v[212:215], v[216:219], v[32:47]
	s_waitcnt lgkmcnt(4)
	v_mfma_f32_32x32x16_bf16 v[48:63], v[212:215], v[220:223], v[48:63]
	ds_read_b128 v[212:215], v96 offset:59936
	s_waitcnt lgkmcnt(4)
	v_mfma_f32_32x32x16_bf16 v[16:31], v[224:227], v[216:219], v[16:31]
	ds_read_b128 v[216:219], v96 offset:55360
	v_mfma_f32_32x32x16_bf16 v[0:15], v[224:227], v[220:223], v[0:15]
	ds_read_b128 v[224:227], v210 offset:18496
	ds_read_b128 v[220:223], v210 offset:23104
	s_waitcnt lgkmcnt(5)
	v_mfma_f32_32x32x16_bf16 v[32:47], v[228:231], v[244:247], v[32:47]
	s_waitcnt lgkmcnt(4)
	v_mfma_f32_32x32x16_bf16 v[48:63], v[228:231], v[252:255], v[48:63]
	ds_read_b128 v[228:231], v96 offset:59968
	s_waitcnt lgkmcnt(4)
	v_mfma_f32_32x32x16_bf16 v[16:31], v[212:215], v[244:247], v[16:31]
	ds_read_b128 v[244:247], v96 offset:55392
	v_mfma_f32_32x32x16_bf16 v[0:15], v[212:215], v[252:255], v[0:15]
	ds_read_b128 v[212:215], v210 offset:18528
	ds_read_b128 v[252:255], v210 offset:23136
	s_waitcnt lgkmcnt(5)
	v_mfma_f32_32x32x16_bf16 v[32:47], v[216:219], v[224:227], v[32:47]
	s_waitcnt vmcnt(15)
	ds_write_b128 v209, v[64:67]
	global_load_dwordx4 v[64:67], v[148:149], off offset:2816
	s_waitcnt lgkmcnt(5)
	v_mfma_f32_32x32x16_bf16 v[48:63], v[216:219], v[220:223], v[48:63]
	ds_read_b128 v[216:219], v96 offset:60000
	s_waitcnt vmcnt(15)
	ds_write_b128 v209, v[72:75] offset:4608
	global_load_dwordx4 v[72:75], v[150:151], off offset:2816
	s_waitcnt lgkmcnt(6)
	v_mfma_f32_32x32x16_bf16 v[16:31], v[228:231], v[224:227], v[16:31]
	s_waitcnt vmcnt(15)
	ds_write_b128 v209, v[76:79] offset:9216
	global_load_dwordx4 v[76:79], v[152:153], off offset:2816
	v_mfma_f32_32x32x16_bf16 v[0:15], v[228:231], v[220:223], v[0:15]
	s_waitcnt vmcnt(15)
	ds_write_b128 v209, v[80:83] offset:13824
	global_load_dwordx4 v[80:83], v[154:155], off offset:2816
	s_waitcnt lgkmcnt(6)
	v_mfma_f32_32x32x16_bf16 v[32:47], v[244:247], v[212:215], v[32:47]
	s_waitcnt vmcnt(15)
	ds_write_b128 v209, v[102:105] offset:36864
	global_load_dwordx4 v[102:105], v[146:147], off offset:2816
	s_waitcnt lgkmcnt(6)
	v_mfma_f32_32x32x16_bf16 v[48:63], v[244:247], v[252:255], v[48:63]
	s_waitcnt vmcnt(15)
	ds_write_b128 v209, v[118:121] offset:41472
	global_load_dwordx4 v[118:121], v[156:157], off offset:2816
	s_waitcnt lgkmcnt(5)
	v_mfma_f32_32x32x16_bf16 v[16:31], v[216:219], v[212:215], v[16:31]
	s_waitcnt vmcnt(15)
	ds_write_b128 v209, v[122:125] offset:46080
	global_load_dwordx4 v[122:125], v[158:159], off offset:2816
	v_mfma_f32_32x32x16_bf16 v[0:15], v[216:219], v[252:255], v[0:15]
	s_waitcnt vmcnt(15)
	ds_write_b128 v209, v[126:129] offset:50688
	global_load_dwordx4 v[126:129], v[160:161], off offset:2816
	s_setprio 0
	s_waitcnt lgkmcnt(0)
	s_barrier
	s_setprio 1
	ds_read_b128 v[212:215], v96 offset:36864
	ds_read_b128 v[216:219], v210
	ds_read_b128 v[220:223], v210 offset:4608
	ds_read_b128 v[224:227], v96 offset:41472
	ds_read_b128 v[228:231], v96 offset:36896
	ds_read_b128 v[244:247], v210 offset:32
	ds_read_b128 v[252:255], v210 offset:4640
	s_waitcnt lgkmcnt(5)
	v_mfma_f32_32x32x16_bf16 v[32:47], v[212:215], v[216:219], v[32:47]
	s_waitcnt lgkmcnt(4)
	v_mfma_f32_32x32x16_bf16 v[48:63], v[212:215], v[220:223], v[48:63]
	ds_read_b128 v[212:215], v96 offset:41504
	s_waitcnt lgkmcnt(4)
	v_mfma_f32_32x32x16_bf16 v[16:31], v[224:227], v[216:219], v[16:31]
	ds_read_b128 v[216:219], v96 offset:36928
	v_mfma_f32_32x32x16_bf16 v[0:15], v[224:227], v[220:223], v[0:15]
	ds_read_b128 v[224:227], v210 offset:64
	ds_read_b128 v[220:223], v210 offset:4672
	s_waitcnt lgkmcnt(5)
	v_mfma_f32_32x32x16_bf16 v[32:47], v[228:231], v[244:247], v[32:47]
	s_waitcnt lgkmcnt(4)
	v_mfma_f32_32x32x16_bf16 v[48:63], v[228:231], v[252:255], v[48:63]
	ds_read_b128 v[228:231], v96 offset:41536
	s_waitcnt lgkmcnt(4)
	v_mfma_f32_32x32x16_bf16 v[16:31], v[212:215], v[244:247], v[16:31]
	ds_read_b128 v[244:247], v96 offset:36960
	v_mfma_f32_32x32x16_bf16 v[0:15], v[212:215], v[252:255], v[0:15]
	ds_read_b128 v[212:215], v210 offset:96
	ds_read_b128 v[252:255], v210 offset:4704
	s_waitcnt lgkmcnt(5)
	v_mfma_f32_32x32x16_bf16 v[32:47], v[216:219], v[224:227], v[32:47]
	s_waitcnt vmcnt(15)
	ds_write_b128 v209, v[68:71] offset:18432
	global_load_dwordx4 v[68:71], v[148:149], off offset:2944
	s_waitcnt lgkmcnt(5)
	v_mfma_f32_32x32x16_bf16 v[48:63], v[216:219], v[220:223], v[48:63]
	ds_read_b128 v[216:219], v96 offset:41568
	s_waitcnt vmcnt(15)
	ds_write_b128 v209, v[84:87] offset:23040
	global_load_dwordx4 v[84:87], v[150:151], off offset:2944
	s_waitcnt lgkmcnt(6)
	v_mfma_f32_32x32x16_bf16 v[16:31], v[228:231], v[224:227], v[16:31]
	s_waitcnt vmcnt(15)
	ds_write_b128 v209, v[88:91] offset:27648
	global_load_dwordx4 v[88:91], v[152:153], off offset:2944
	v_mfma_f32_32x32x16_bf16 v[0:15], v[228:231], v[220:223], v[0:15]
	s_waitcnt vmcnt(15)
	ds_write_b128 v209, v[92:95] offset:32256
	global_load_dwordx4 v[92:95], v[154:155], off offset:2944
	s_waitcnt lgkmcnt(6)
	v_mfma_f32_32x32x16_bf16 v[32:47], v[244:247], v[212:215], v[32:47]
	s_waitcnt vmcnt(15)
	ds_write_b128 v209, v[98:101] offset:55296
	global_load_dwordx4 v[98:101], v[146:147], off offset:2944
	s_waitcnt lgkmcnt(6)
	v_mfma_f32_32x32x16_bf16 v[48:63], v[244:247], v[252:255], v[48:63]
	s_waitcnt vmcnt(15)
	ds_write_b128 v209, v[106:109] offset:59904
	global_load_dwordx4 v[106:109], v[156:157], off offset:2944
	s_waitcnt lgkmcnt(5)
	v_mfma_f32_32x32x16_bf16 v[16:31], v[216:219], v[212:215], v[16:31]
	s_waitcnt vmcnt(15)
	ds_write_b128 v209, v[110:113] offset:64512
	global_load_dwordx4 v[110:113], v[158:159], off offset:2944
	v_mfma_f32_32x32x16_bf16 v[0:15], v[216:219], v[252:255], v[0:15]
	s_waitcnt vmcnt(15)
	ds_write_b128 v211, v[114:117] offset:13824
	global_load_dwordx4 v[114:117], v[160:161], off offset:2944
	s_setprio 0
	s_waitcnt lgkmcnt(0)
	s_barrier
	s_setprio 1
	ds_read_b128 v[212:215], v96 offset:55296
	ds_read_b128 v[216:219], v210 offset:18432
	ds_read_b128 v[220:223], v210 offset:23040
	ds_read_b128 v[224:227], v96 offset:59904
	ds_read_b128 v[228:231], v96 offset:55328
	ds_read_b128 v[244:247], v210 offset:18464
	ds_read_b128 v[252:255], v210 offset:23072
	s_waitcnt lgkmcnt(5)
	v_mfma_f32_32x32x16_bf16 v[32:47], v[212:215], v[216:219], v[32:47]
	s_waitcnt lgkmcnt(4)
	v_mfma_f32_32x32x16_bf16 v[48:63], v[212:215], v[220:223], v[48:63]
	ds_read_b128 v[212:215], v96 offset:59936
	s_waitcnt lgkmcnt(4)
	v_mfma_f32_32x32x16_bf16 v[16:31], v[224:227], v[216:219], v[16:31]
	ds_read_b128 v[216:219], v96 offset:55360
	v_mfma_f32_32x32x16_bf16 v[0:15], v[224:227], v[220:223], v[0:15]
	ds_read_b128 v[224:227], v210 offset:18496
	ds_read_b128 v[220:223], v210 offset:23104
	s_waitcnt lgkmcnt(5)
	v_mfma_f32_32x32x16_bf16 v[32:47], v[228:231], v[244:247], v[32:47]
	s_waitcnt lgkmcnt(4)
	v_mfma_f32_32x32x16_bf16 v[48:63], v[228:231], v[252:255], v[48:63]
	ds_read_b128 v[228:231], v96 offset:59968
	s_waitcnt lgkmcnt(4)
	v_mfma_f32_32x32x16_bf16 v[16:31], v[212:215], v[244:247], v[16:31]
	ds_read_b128 v[244:247], v96 offset:55392
	v_mfma_f32_32x32x16_bf16 v[0:15], v[212:215], v[252:255], v[0:15]
	ds_read_b128 v[212:215], v210 offset:18528
	ds_read_b128 v[252:255], v210 offset:23136
	s_waitcnt lgkmcnt(5)
	v_mfma_f32_32x32x16_bf16 v[32:47], v[216:219], v[224:227], v[32:47]
	s_waitcnt vmcnt(15)
	ds_write_b128 v209, v[64:67]
	global_load_dwordx4 v[64:67], v[148:149], off offset:3072
	s_waitcnt lgkmcnt(5)
	v_mfma_f32_32x32x16_bf16 v[48:63], v[216:219], v[220:223], v[48:63]
	ds_read_b128 v[216:219], v96 offset:60000
	s_waitcnt vmcnt(15)
	ds_write_b128 v209, v[72:75] offset:4608
	global_load_dwordx4 v[72:75], v[150:151], off offset:3072
	s_waitcnt lgkmcnt(6)
	v_mfma_f32_32x32x16_bf16 v[16:31], v[228:231], v[224:227], v[16:31]
	s_waitcnt vmcnt(15)
	ds_write_b128 v209, v[76:79] offset:9216
	global_load_dwordx4 v[76:79], v[152:153], off offset:3072
	v_mfma_f32_32x32x16_bf16 v[0:15], v[228:231], v[220:223], v[0:15]
	s_waitcnt vmcnt(15)
	ds_write_b128 v209, v[80:83] offset:13824
	global_load_dwordx4 v[80:83], v[154:155], off offset:3072
	s_waitcnt lgkmcnt(6)
	v_mfma_f32_32x32x16_bf16 v[32:47], v[244:247], v[212:215], v[32:47]
	s_waitcnt vmcnt(15)
	ds_write_b128 v209, v[102:105] offset:36864
	global_load_dwordx4 v[102:105], v[146:147], off offset:3072
	s_waitcnt lgkmcnt(6)
	v_mfma_f32_32x32x16_bf16 v[48:63], v[244:247], v[252:255], v[48:63]
	s_waitcnt vmcnt(15)
	ds_write_b128 v209, v[118:121] offset:41472
	global_load_dwordx4 v[118:121], v[156:157], off offset:3072
	s_waitcnt lgkmcnt(5)
	v_mfma_f32_32x32x16_bf16 v[16:31], v[216:219], v[212:215], v[16:31]
	s_waitcnt vmcnt(15)
	ds_write_b128 v209, v[122:125] offset:46080
	global_load_dwordx4 v[122:125], v[158:159], off offset:3072
	v_mfma_f32_32x32x16_bf16 v[0:15], v[216:219], v[252:255], v[0:15]
	s_waitcnt vmcnt(15)
	ds_write_b128 v209, v[126:129] offset:50688
	global_load_dwordx4 v[126:129], v[160:161], off offset:3072
	s_setprio 0
	s_waitcnt lgkmcnt(0)
	s_barrier
	s_setprio 1
	ds_read_b128 v[212:215], v96 offset:36864
	ds_read_b128 v[216:219], v210
	ds_read_b128 v[220:223], v210 offset:4608
	ds_read_b128 v[224:227], v96 offset:41472
	ds_read_b128 v[228:231], v96 offset:36896
	ds_read_b128 v[244:247], v210 offset:32
	ds_read_b128 v[252:255], v210 offset:4640
	s_waitcnt lgkmcnt(5)
	v_mfma_f32_32x32x16_bf16 v[32:47], v[212:215], v[216:219], v[32:47]
	s_waitcnt lgkmcnt(4)
	v_mfma_f32_32x32x16_bf16 v[48:63], v[212:215], v[220:223], v[48:63]
	ds_read_b128 v[212:215], v96 offset:41504
	s_waitcnt lgkmcnt(4)
	v_mfma_f32_32x32x16_bf16 v[16:31], v[224:227], v[216:219], v[16:31]
	ds_read_b128 v[216:219], v96 offset:36928
	v_mfma_f32_32x32x16_bf16 v[0:15], v[224:227], v[220:223], v[0:15]
	ds_read_b128 v[224:227], v210 offset:64
	ds_read_b128 v[220:223], v210 offset:4672
	s_waitcnt lgkmcnt(5)
	v_mfma_f32_32x32x16_bf16 v[32:47], v[228:231], v[244:247], v[32:47]
	s_waitcnt lgkmcnt(4)
	v_mfma_f32_32x32x16_bf16 v[48:63], v[228:231], v[252:255], v[48:63]
	ds_read_b128 v[228:231], v96 offset:41536
	s_waitcnt lgkmcnt(4)
	v_mfma_f32_32x32x16_bf16 v[16:31], v[212:215], v[244:247], v[16:31]
	ds_read_b128 v[244:247], v96 offset:36960
	v_mfma_f32_32x32x16_bf16 v[0:15], v[212:215], v[252:255], v[0:15]
	ds_read_b128 v[212:215], v210 offset:96
	ds_read_b128 v[252:255], v210 offset:4704
	s_waitcnt lgkmcnt(5)
	v_mfma_f32_32x32x16_bf16 v[32:47], v[216:219], v[224:227], v[32:47]
	s_waitcnt vmcnt(15)
	ds_write_b128 v209, v[68:71] offset:18432
	global_load_dwordx4 v[68:71], v[148:149], off offset:3200
	s_waitcnt lgkmcnt(5)
	v_mfma_f32_32x32x16_bf16 v[48:63], v[216:219], v[220:223], v[48:63]
	ds_read_b128 v[216:219], v96 offset:41568
	s_waitcnt vmcnt(15)
	ds_write_b128 v209, v[84:87] offset:23040
	global_load_dwordx4 v[84:87], v[150:151], off offset:3200
	s_waitcnt lgkmcnt(6)
	v_mfma_f32_32x32x16_bf16 v[16:31], v[228:231], v[224:227], v[16:31]
	s_waitcnt vmcnt(15)
	ds_write_b128 v209, v[88:91] offset:27648
	global_load_dwordx4 v[88:91], v[152:153], off offset:3200
	v_mfma_f32_32x32x16_bf16 v[0:15], v[228:231], v[220:223], v[0:15]
	s_waitcnt vmcnt(15)
	ds_write_b128 v209, v[92:95] offset:32256
	global_load_dwordx4 v[92:95], v[154:155], off offset:3200
	s_waitcnt lgkmcnt(6)
	v_mfma_f32_32x32x16_bf16 v[32:47], v[244:247], v[212:215], v[32:47]
	s_waitcnt vmcnt(15)
	ds_write_b128 v209, v[98:101] offset:55296
	global_load_dwordx4 v[98:101], v[146:147], off offset:3200
	s_waitcnt lgkmcnt(6)
	v_mfma_f32_32x32x16_bf16 v[48:63], v[244:247], v[252:255], v[48:63]
	s_waitcnt vmcnt(15)
	ds_write_b128 v209, v[106:109] offset:59904
	global_load_dwordx4 v[106:109], v[156:157], off offset:3200
	s_waitcnt lgkmcnt(5)
	v_mfma_f32_32x32x16_bf16 v[16:31], v[216:219], v[212:215], v[16:31]
	s_waitcnt vmcnt(15)
	ds_write_b128 v209, v[110:113] offset:64512
	global_load_dwordx4 v[110:113], v[158:159], off offset:3200
	v_mfma_f32_32x32x16_bf16 v[0:15], v[216:219], v[252:255], v[0:15]
	s_waitcnt vmcnt(15)
	ds_write_b128 v211, v[114:117] offset:13824
	global_load_dwordx4 v[114:117], v[160:161], off offset:3200
	s_setprio 0
	s_waitcnt lgkmcnt(0)
	s_barrier
	s_setprio 1
	ds_read_b128 v[212:215], v96 offset:55296
	ds_read_b128 v[216:219], v210 offset:18432
	ds_read_b128 v[220:223], v210 offset:23040
	ds_read_b128 v[224:227], v96 offset:59904
	ds_read_b128 v[228:231], v96 offset:55328
	ds_read_b128 v[244:247], v210 offset:18464
	ds_read_b128 v[252:255], v210 offset:23072
	s_waitcnt lgkmcnt(5)
	v_mfma_f32_32x32x16_bf16 v[32:47], v[212:215], v[216:219], v[32:47]
	s_waitcnt lgkmcnt(4)
	v_mfma_f32_32x32x16_bf16 v[48:63], v[212:215], v[220:223], v[48:63]
	ds_read_b128 v[212:215], v96 offset:59936
	s_waitcnt lgkmcnt(4)
	v_mfma_f32_32x32x16_bf16 v[16:31], v[224:227], v[216:219], v[16:31]
	ds_read_b128 v[216:219], v96 offset:55360
	v_mfma_f32_32x32x16_bf16 v[0:15], v[224:227], v[220:223], v[0:15]
	ds_read_b128 v[224:227], v210 offset:18496
	ds_read_b128 v[220:223], v210 offset:23104
	s_waitcnt lgkmcnt(5)
	v_mfma_f32_32x32x16_bf16 v[32:47], v[228:231], v[244:247], v[32:47]
	s_waitcnt lgkmcnt(4)
	v_mfma_f32_32x32x16_bf16 v[48:63], v[228:231], v[252:255], v[48:63]
	ds_read_b128 v[228:231], v96 offset:59968
	s_waitcnt lgkmcnt(4)
	v_mfma_f32_32x32x16_bf16 v[16:31], v[212:215], v[244:247], v[16:31]
	ds_read_b128 v[244:247], v96 offset:55392
	v_mfma_f32_32x32x16_bf16 v[0:15], v[212:215], v[252:255], v[0:15]
	ds_read_b128 v[212:215], v210 offset:18528
	ds_read_b128 v[252:255], v210 offset:23136
	s_waitcnt lgkmcnt(5)
	v_mfma_f32_32x32x16_bf16 v[32:47], v[216:219], v[224:227], v[32:47]
	s_waitcnt vmcnt(15)
	ds_write_b128 v209, v[64:67]
	global_load_dwordx4 v[64:67], v[148:149], off offset:3328
	s_waitcnt lgkmcnt(5)
	v_mfma_f32_32x32x16_bf16 v[48:63], v[216:219], v[220:223], v[48:63]
	ds_read_b128 v[216:219], v96 offset:60000
	s_waitcnt vmcnt(15)
	ds_write_b128 v209, v[72:75] offset:4608
	global_load_dwordx4 v[72:75], v[150:151], off offset:3328
	s_waitcnt lgkmcnt(6)
	v_mfma_f32_32x32x16_bf16 v[16:31], v[228:231], v[224:227], v[16:31]
	s_waitcnt vmcnt(15)
	ds_write_b128 v209, v[76:79] offset:9216
	global_load_dwordx4 v[76:79], v[152:153], off offset:3328
	v_mfma_f32_32x32x16_bf16 v[0:15], v[228:231], v[220:223], v[0:15]
	s_waitcnt vmcnt(15)
	ds_write_b128 v209, v[80:83] offset:13824
	global_load_dwordx4 v[80:83], v[154:155], off offset:3328
	s_waitcnt lgkmcnt(6)
	v_mfma_f32_32x32x16_bf16 v[32:47], v[244:247], v[212:215], v[32:47]
	s_waitcnt vmcnt(15)
	ds_write_b128 v209, v[102:105] offset:36864
	global_load_dwordx4 v[102:105], v[146:147], off offset:3328
	s_waitcnt lgkmcnt(6)
	v_mfma_f32_32x32x16_bf16 v[48:63], v[244:247], v[252:255], v[48:63]
	s_waitcnt vmcnt(15)
	ds_write_b128 v209, v[118:121] offset:41472
	global_load_dwordx4 v[118:121], v[156:157], off offset:3328
	s_waitcnt lgkmcnt(5)
	v_mfma_f32_32x32x16_bf16 v[16:31], v[216:219], v[212:215], v[16:31]
	s_waitcnt vmcnt(15)
	ds_write_b128 v209, v[122:125] offset:46080
	global_load_dwordx4 v[122:125], v[158:159], off offset:3328
	v_mfma_f32_32x32x16_bf16 v[0:15], v[216:219], v[252:255], v[0:15]
	s_waitcnt vmcnt(15)
	ds_write_b128 v209, v[126:129] offset:50688
	global_load_dwordx4 v[126:129], v[160:161], off offset:3328
	s_setprio 0
	s_waitcnt lgkmcnt(0)
	s_barrier
	s_setprio 1
	ds_read_b128 v[212:215], v96 offset:36864
	ds_read_b128 v[216:219], v210
	ds_read_b128 v[220:223], v210 offset:4608
	ds_read_b128 v[224:227], v96 offset:41472
	ds_read_b128 v[228:231], v96 offset:36896
	ds_read_b128 v[244:247], v210 offset:32
	ds_read_b128 v[252:255], v210 offset:4640
	s_waitcnt lgkmcnt(5)
	v_mfma_f32_32x32x16_bf16 v[32:47], v[212:215], v[216:219], v[32:47]
	s_waitcnt lgkmcnt(4)
	v_mfma_f32_32x32x16_bf16 v[48:63], v[212:215], v[220:223], v[48:63]
	ds_read_b128 v[212:215], v96 offset:41504
	s_waitcnt lgkmcnt(4)
	v_mfma_f32_32x32x16_bf16 v[16:31], v[224:227], v[216:219], v[16:31]
	ds_read_b128 v[216:219], v96 offset:36928
	v_mfma_f32_32x32x16_bf16 v[0:15], v[224:227], v[220:223], v[0:15]
	ds_read_b128 v[224:227], v210 offset:64
	ds_read_b128 v[220:223], v210 offset:4672
	s_waitcnt lgkmcnt(5)
	v_mfma_f32_32x32x16_bf16 v[32:47], v[228:231], v[244:247], v[32:47]
	s_waitcnt lgkmcnt(4)
	v_mfma_f32_32x32x16_bf16 v[48:63], v[228:231], v[252:255], v[48:63]
	ds_read_b128 v[228:231], v96 offset:41536
	s_waitcnt lgkmcnt(4)
	v_mfma_f32_32x32x16_bf16 v[16:31], v[212:215], v[244:247], v[16:31]
	ds_read_b128 v[244:247], v96 offset:36960
	v_mfma_f32_32x32x16_bf16 v[0:15], v[212:215], v[252:255], v[0:15]
	ds_read_b128 v[212:215], v210 offset:96
	ds_read_b128 v[252:255], v210 offset:4704
	s_waitcnt lgkmcnt(5)
	v_mfma_f32_32x32x16_bf16 v[32:47], v[216:219], v[224:227], v[32:47]
	s_waitcnt vmcnt(15)
	ds_write_b128 v209, v[68:71] offset:18432
	global_load_dwordx4 v[68:71], v[148:149], off offset:3456
	s_waitcnt lgkmcnt(5)
	v_mfma_f32_32x32x16_bf16 v[48:63], v[216:219], v[220:223], v[48:63]
	ds_read_b128 v[216:219], v96 offset:41568
	s_waitcnt vmcnt(15)
	ds_write_b128 v209, v[84:87] offset:23040
	global_load_dwordx4 v[84:87], v[150:151], off offset:3456
	s_waitcnt lgkmcnt(6)
	v_mfma_f32_32x32x16_bf16 v[16:31], v[228:231], v[224:227], v[16:31]
	s_waitcnt vmcnt(15)
	ds_write_b128 v209, v[88:91] offset:27648
	global_load_dwordx4 v[88:91], v[152:153], off offset:3456
	v_mfma_f32_32x32x16_bf16 v[0:15], v[228:231], v[220:223], v[0:15]
	s_waitcnt vmcnt(15)
	ds_write_b128 v209, v[92:95] offset:32256
	global_load_dwordx4 v[92:95], v[154:155], off offset:3456
	s_waitcnt lgkmcnt(6)
	v_mfma_f32_32x32x16_bf16 v[32:47], v[244:247], v[212:215], v[32:47]
	s_waitcnt vmcnt(15)
	ds_write_b128 v209, v[98:101] offset:55296
	global_load_dwordx4 v[98:101], v[146:147], off offset:3456
	s_waitcnt lgkmcnt(6)
	v_mfma_f32_32x32x16_bf16 v[48:63], v[244:247], v[252:255], v[48:63]
	s_waitcnt vmcnt(15)
	ds_write_b128 v209, v[106:109] offset:59904
	global_load_dwordx4 v[106:109], v[156:157], off offset:3456
	s_waitcnt lgkmcnt(5)
	v_mfma_f32_32x32x16_bf16 v[16:31], v[216:219], v[212:215], v[16:31]
	s_waitcnt vmcnt(15)
	ds_write_b128 v209, v[110:113] offset:64512
	global_load_dwordx4 v[110:113], v[158:159], off offset:3456
	v_mfma_f32_32x32x16_bf16 v[0:15], v[216:219], v[252:255], v[0:15]
	s_waitcnt vmcnt(15)
	ds_write_b128 v211, v[114:117] offset:13824
	global_load_dwordx4 v[114:117], v[160:161], off offset:3456
	s_setprio 0
	s_waitcnt lgkmcnt(0)
	s_barrier
	s_setprio 1
	ds_read_b128 v[212:215], v96 offset:55296
	ds_read_b128 v[216:219], v210 offset:18432
	ds_read_b128 v[220:223], v210 offset:23040
	ds_read_b128 v[224:227], v96 offset:59904
	ds_read_b128 v[228:231], v96 offset:55328
	ds_read_b128 v[244:247], v210 offset:18464
	ds_read_b128 v[252:255], v210 offset:23072
	s_waitcnt lgkmcnt(5)
	v_mfma_f32_32x32x16_bf16 v[32:47], v[212:215], v[216:219], v[32:47]
	s_waitcnt lgkmcnt(4)
	v_mfma_f32_32x32x16_bf16 v[48:63], v[212:215], v[220:223], v[48:63]
	ds_read_b128 v[212:215], v96 offset:59936
	s_waitcnt lgkmcnt(4)
	v_mfma_f32_32x32x16_bf16 v[16:31], v[224:227], v[216:219], v[16:31]
	ds_read_b128 v[216:219], v96 offset:55360
	v_mfma_f32_32x32x16_bf16 v[0:15], v[224:227], v[220:223], v[0:15]
	ds_read_b128 v[224:227], v210 offset:18496
	ds_read_b128 v[220:223], v210 offset:23104
	s_waitcnt lgkmcnt(5)
	v_mfma_f32_32x32x16_bf16 v[32:47], v[228:231], v[244:247], v[32:47]
	s_waitcnt lgkmcnt(4)
	v_mfma_f32_32x32x16_bf16 v[48:63], v[228:231], v[252:255], v[48:63]
	ds_read_b128 v[228:231], v96 offset:59968
	s_waitcnt lgkmcnt(4)
	v_mfma_f32_32x32x16_bf16 v[16:31], v[212:215], v[244:247], v[16:31]
	ds_read_b128 v[244:247], v96 offset:55392
	v_mfma_f32_32x32x16_bf16 v[0:15], v[212:215], v[252:255], v[0:15]
	ds_read_b128 v[212:215], v210 offset:18528
	ds_read_b128 v[252:255], v210 offset:23136
	s_waitcnt lgkmcnt(5)
	v_mfma_f32_32x32x16_bf16 v[32:47], v[216:219], v[224:227], v[32:47]
	s_waitcnt vmcnt(15)
	ds_write_b128 v209, v[64:67]
	global_load_dwordx4 v[64:67], v[148:149], off offset:3584
	s_waitcnt lgkmcnt(5)
	v_mfma_f32_32x32x16_bf16 v[48:63], v[216:219], v[220:223], v[48:63]
	ds_read_b128 v[216:219], v96 offset:60000
	s_waitcnt vmcnt(15)
	ds_write_b128 v209, v[72:75] offset:4608
	global_load_dwordx4 v[72:75], v[150:151], off offset:3584
	s_waitcnt lgkmcnt(6)
	v_mfma_f32_32x32x16_bf16 v[16:31], v[228:231], v[224:227], v[16:31]
	s_waitcnt vmcnt(15)
	ds_write_b128 v209, v[76:79] offset:9216
	global_load_dwordx4 v[76:79], v[152:153], off offset:3584
	v_mfma_f32_32x32x16_bf16 v[0:15], v[228:231], v[220:223], v[0:15]
	s_waitcnt vmcnt(15)
	ds_write_b128 v209, v[80:83] offset:13824
	global_load_dwordx4 v[80:83], v[154:155], off offset:3584
	s_waitcnt lgkmcnt(6)
	v_mfma_f32_32x32x16_bf16 v[32:47], v[244:247], v[212:215], v[32:47]
	s_waitcnt vmcnt(15)
	ds_write_b128 v209, v[102:105] offset:36864
	global_load_dwordx4 v[102:105], v[146:147], off offset:3584
	s_waitcnt lgkmcnt(6)
	v_mfma_f32_32x32x16_bf16 v[48:63], v[244:247], v[252:255], v[48:63]
	s_waitcnt vmcnt(15)
	ds_write_b128 v209, v[118:121] offset:41472
	global_load_dwordx4 v[118:121], v[156:157], off offset:3584
	s_waitcnt lgkmcnt(5)
	v_mfma_f32_32x32x16_bf16 v[16:31], v[216:219], v[212:215], v[16:31]
	s_waitcnt vmcnt(15)
	ds_write_b128 v209, v[122:125] offset:46080
	global_load_dwordx4 v[122:125], v[158:159], off offset:3584
	v_mfma_f32_32x32x16_bf16 v[0:15], v[216:219], v[252:255], v[0:15]
	s_waitcnt vmcnt(15)
	ds_write_b128 v209, v[126:129] offset:50688
	global_load_dwordx4 v[126:129], v[160:161], off offset:3584
	s_setprio 0
	s_waitcnt lgkmcnt(0)
	s_barrier
	s_setprio 1
	ds_read_b128 v[212:215], v96 offset:36864
	ds_read_b128 v[216:219], v210
	ds_read_b128 v[220:223], v210 offset:4608
	ds_read_b128 v[224:227], v96 offset:41472
	ds_read_b128 v[228:231], v96 offset:36896
	ds_read_b128 v[244:247], v210 offset:32
	ds_read_b128 v[252:255], v210 offset:4640
	s_waitcnt lgkmcnt(5)
	v_mfma_f32_32x32x16_bf16 v[32:47], v[212:215], v[216:219], v[32:47]
	s_waitcnt lgkmcnt(4)
	v_mfma_f32_32x32x16_bf16 v[48:63], v[212:215], v[220:223], v[48:63]
	ds_read_b128 v[212:215], v96 offset:41504
	s_waitcnt lgkmcnt(4)
	v_mfma_f32_32x32x16_bf16 v[16:31], v[224:227], v[216:219], v[16:31]
	ds_read_b128 v[216:219], v96 offset:36928
	v_mfma_f32_32x32x16_bf16 v[0:15], v[224:227], v[220:223], v[0:15]
	ds_read_b128 v[224:227], v210 offset:64
	ds_read_b128 v[220:223], v210 offset:4672
	s_waitcnt lgkmcnt(5)
	v_mfma_f32_32x32x16_bf16 v[32:47], v[228:231], v[244:247], v[32:47]
	s_waitcnt lgkmcnt(4)
	v_mfma_f32_32x32x16_bf16 v[48:63], v[228:231], v[252:255], v[48:63]
	ds_read_b128 v[228:231], v96 offset:41536
	s_waitcnt lgkmcnt(4)
	v_mfma_f32_32x32x16_bf16 v[16:31], v[212:215], v[244:247], v[16:31]
	ds_read_b128 v[244:247], v96 offset:36960
	v_mfma_f32_32x32x16_bf16 v[0:15], v[212:215], v[252:255], v[0:15]
	ds_read_b128 v[212:215], v210 offset:96
	ds_read_b128 v[252:255], v210 offset:4704
	s_waitcnt lgkmcnt(5)
	v_mfma_f32_32x32x16_bf16 v[32:47], v[216:219], v[224:227], v[32:47]
	s_waitcnt vmcnt(15)
	ds_write_b128 v209, v[68:71] offset:18432
	global_load_dwordx4 v[68:71], v[148:149], off offset:3712
	s_waitcnt vmcnt(15)
	s_waitcnt lgkmcnt(5)
	v_mfma_f32_32x32x16_bf16 v[48:63], v[216:219], v[220:223], v[48:63]
	ds_read_b128 v[216:219], v96 offset:41568
	ds_write_b128 v209, v[84:87] offset:23040
	global_load_dwordx4 v[84:87], v[150:151], off offset:3712
	s_waitcnt vmcnt(15)
	s_waitcnt lgkmcnt(6)
	v_mfma_f32_32x32x16_bf16 v[16:31], v[228:231], v[224:227], v[16:31]
	ds_write_b128 v209, v[88:91] offset:27648
	global_load_dwordx4 v[88:91], v[152:153], off offset:3712
	s_waitcnt vmcnt(15)
	v_mfma_f32_32x32x16_bf16 v[0:15], v[228:231], v[220:223], v[0:15]
	ds_write_b128 v209, v[92:95] offset:32256
	global_load_dwordx4 v[92:95], v[154:155], off offset:3712
	s_waitcnt vmcnt(15)
	s_waitcnt lgkmcnt(6)
	v_mfma_f32_32x32x16_bf16 v[32:47], v[244:247], v[212:215], v[32:47]
	ds_write_b128 v209, v[98:101] offset:55296
	s_waitcnt vmcnt(14)
	ds_write_b128 v209, v[106:109] offset:59904
	s_waitcnt lgkmcnt(7)
	v_mfma_f32_32x32x16_bf16 v[48:63], v[244:247], v[252:255], v[48:63]
	s_waitcnt vmcnt(13)
	ds_write_b128 v209, v[110:113] offset:64512
	s_waitcnt vmcnt(12)
	ds_write_b128 v211, v[114:117] offset:13824
	s_waitcnt lgkmcnt(7)
	v_mfma_f32_32x32x16_bf16 v[16:31], v[216:219], v[212:215], v[16:31]
	global_load_dwordx4 v[114:117], v[146:147], off offset:3712
	global_load_dwordx4 v[130:133], v[156:157], off offset:3712
	v_mfma_f32_32x32x16_bf16 v[0:15], v[216:219], v[252:255], v[0:15]
	global_load_dwordx4 v[134:137], v[158:159], off offset:3712
	global_load_dwordx4 v[138:141], v[160:161], off offset:3712
	s_setprio 0
	s_waitcnt lgkmcnt(0)
	s_barrier
	s_setprio 1
	ds_read_b128 v[212:215], v96 offset:55296
	ds_read_b128 v[216:219], v210 offset:18432
	ds_read_b128 v[220:223], v210 offset:23040
	ds_read_b128 v[224:227], v96 offset:59904
	ds_read_b128 v[228:231], v96 offset:55328
	ds_read_b128 v[244:247], v210 offset:18464
	ds_read_b128 v[252:255], v210 offset:23072
	s_waitcnt lgkmcnt(5)
	v_mfma_f32_32x32x16_bf16 v[32:47], v[212:215], v[216:219], v[32:47]
	s_waitcnt lgkmcnt(4)
	v_mfma_f32_32x32x16_bf16 v[48:63], v[212:215], v[220:223], v[48:63]
	ds_read_b128 v[212:215], v96 offset:59936
	s_waitcnt lgkmcnt(4)
	v_mfma_f32_32x32x16_bf16 v[16:31], v[224:227], v[216:219], v[16:31]
	ds_read_b128 v[216:219], v96 offset:55360
	v_mfma_f32_32x32x16_bf16 v[0:15], v[224:227], v[220:223], v[0:15]
	ds_read_b128 v[224:227], v210 offset:18496
	ds_read_b128 v[220:223], v210 offset:23104
	s_waitcnt lgkmcnt(5)
	v_mfma_f32_32x32x16_bf16 v[32:47], v[228:231], v[244:247], v[32:47]
	s_waitcnt lgkmcnt(4)
	v_mfma_f32_32x32x16_bf16 v[48:63], v[228:231], v[252:255], v[48:63]
	ds_read_b128 v[228:231], v96 offset:59968
	s_waitcnt lgkmcnt(4)
	v_mfma_f32_32x32x16_bf16 v[16:31], v[212:215], v[244:247], v[16:31]
	ds_read_b128 v[244:247], v96 offset:55392
	v_mfma_f32_32x32x16_bf16 v[0:15], v[212:215], v[252:255], v[0:15]
	ds_read_b128 v[212:215], v210 offset:18528
	ds_read_b128 v[252:255], v210 offset:23136
	s_waitcnt lgkmcnt(5)
	v_mfma_f32_32x32x16_bf16 v[32:47], v[216:219], v[224:227], v[32:47]
	s_waitcnt vmcnt(15)
	ds_write_b128 v209, v[64:67]
	global_load_dwordx4 v[98:101], v[148:149], off offset:3840
	s_waitcnt lgkmcnt(5)
	v_mfma_f32_32x32x16_bf16 v[48:63], v[216:219], v[220:223], v[48:63]
	ds_read_b128 v[216:219], v96 offset:60000
	s_waitcnt vmcnt(15)
	ds_write_b128 v209, v[72:75] offset:4608
	s_waitcnt vmcnt(14)
	ds_write_b128 v209, v[76:79] offset:9216
	s_waitcnt lgkmcnt(7)
	v_mfma_f32_32x32x16_bf16 v[16:31], v[228:231], v[224:227], v[16:31]
	s_waitcnt vmcnt(13)
	ds_write_b128 v209, v[80:83] offset:13824
	s_waitcnt vmcnt(12)
	ds_write_b128 v209, v[102:105] offset:36864
	v_mfma_f32_32x32x16_bf16 v[0:15], v[228:231], v[220:223], v[0:15]
	global_load_dwordx4 v[102:105], v[150:151], off offset:3840
	global_load_dwordx4 v[106:109], v[152:153], off offset:3840
	s_waitcnt lgkmcnt(7)
	v_mfma_f32_32x32x16_bf16 v[32:47], v[244:247], v[212:215], v[32:47]
	global_load_dwordx4 v[110:113], v[154:155], off offset:3840
	s_waitcnt vmcnt(14)
	ds_write_b128 v209, v[118:121] offset:41472
	s_waitcnt lgkmcnt(7)
	v_mfma_f32_32x32x16_bf16 v[48:63], v[244:247], v[252:255], v[48:63]
	global_load_dwordx4 v[118:121], v[146:147], off offset:3840
	s_waitcnt vmcnt(14)
	ds_write_b128 v209, v[122:125] offset:46080
	s_waitcnt lgkmcnt(6)
	v_mfma_f32_32x32x16_bf16 v[16:31], v[216:219], v[212:215], v[16:31]
	global_load_dwordx4 v[122:125], v[156:157], off offset:3840
	s_waitcnt vmcnt(14)
	ds_write_b128 v209, v[126:129] offset:50688
	v_mfma_f32_32x32x16_bf16 v[0:15], v[216:219], v[252:255], v[0:15]
	global_load_dwordx4 v[126:129], v[158:159], off offset:3840
	global_load_dwordx4 v[142:145], v[160:161], off offset:3840
	s_setprio 0
	s_waitcnt lgkmcnt(0)
	s_barrier
	s_setprio 1
	ds_read_b128 v[212:215], v96 offset:36864
	ds_read_b128 v[216:219], v210
	ds_read_b128 v[220:223], v210 offset:4608
	ds_read_b128 v[224:227], v96 offset:41472
	ds_read_b128 v[228:231], v96 offset:36896
	ds_read_b128 v[244:247], v210 offset:32
	ds_read_b128 v[252:255], v210 offset:4640
	s_waitcnt lgkmcnt(5)
	v_mfma_f32_32x32x16_bf16 v[32:47], v[212:215], v[216:219], v[32:47]
	s_waitcnt lgkmcnt(4)
	v_mfma_f32_32x32x16_bf16 v[48:63], v[212:215], v[220:223], v[48:63]
	ds_read_b128 v[212:215], v96 offset:41504
	s_waitcnt lgkmcnt(4)
	v_mfma_f32_32x32x16_bf16 v[16:31], v[224:227], v[216:219], v[16:31]
	ds_read_b128 v[216:219], v96 offset:36928
	v_mfma_f32_32x32x16_bf16 v[0:15], v[224:227], v[220:223], v[0:15]
	ds_read_b128 v[224:227], v210 offset:64
	ds_read_b128 v[220:223], v210 offset:4672
	s_waitcnt lgkmcnt(5)
	v_mfma_f32_32x32x16_bf16 v[32:47], v[228:231], v[244:247], v[32:47]
	s_waitcnt lgkmcnt(4)
	v_mfma_f32_32x32x16_bf16 v[48:63], v[228:231], v[252:255], v[48:63]
	ds_read_b128 v[228:231], v96 offset:41536
	s_waitcnt lgkmcnt(4)
	v_mfma_f32_32x32x16_bf16 v[16:31], v[212:215], v[244:247], v[16:31]
	ds_read_b128 v[244:247], v96 offset:36960
	v_mfma_f32_32x32x16_bf16 v[0:15], v[212:215], v[252:255], v[0:15]
	ds_read_b128 v[212:215], v210 offset:96
	ds_read_b128 v[252:255], v210 offset:4704
	s_waitcnt lgkmcnt(5)
	v_mfma_f32_32x32x16_bf16 v[32:47], v[216:219], v[224:227], v[32:47]
	s_waitcnt vmcnt(15)
	ds_write_b128 v209, v[68:71] offset:18432
	global_load_dwordx4 v[64:67], v[148:149], off offset:3968
	s_waitcnt lgkmcnt(5)
	v_mfma_f32_32x32x16_bf16 v[48:63], v[216:219], v[220:223], v[48:63]
	ds_read_b128 v[216:219], v96 offset:41568
	s_waitcnt vmcnt(15)
	ds_write_b128 v209, v[84:87] offset:23040
	global_load_dwordx4 v[68:71], v[150:151], off offset:3968
	s_waitcnt lgkmcnt(6)
	v_mfma_f32_32x32x16_bf16 v[16:31], v[228:231], v[224:227], v[16:31]
	s_waitcnt vmcnt(15)
	ds_write_b128 v209, v[88:91] offset:27648
	global_load_dwordx4 v[72:75], v[152:153], off offset:3968
	v_mfma_f32_32x32x16_bf16 v[0:15], v[228:231], v[220:223], v[0:15]
	s_waitcnt vmcnt(15)
	ds_write_b128 v209, v[92:95] offset:32256
	global_load_dwordx4 v[76:79], v[154:155], off offset:3968
	s_waitcnt lgkmcnt(6)
	v_mfma_f32_32x32x16_bf16 v[32:47], v[244:247], v[212:215], v[32:47]
	s_waitcnt vmcnt(15)
	ds_write_b128 v209, v[114:117] offset:55296
	global_load_dwordx4 v[80:83], v[146:147], off offset:3968
	s_waitcnt lgkmcnt(6)
	v_mfma_f32_32x32x16_bf16 v[48:63], v[244:247], v[252:255], v[48:63]
	s_waitcnt vmcnt(15)
	ds_write_b128 v209, v[130:133] offset:59904
	global_load_dwordx4 v[84:87], v[156:157], off offset:3968
	s_waitcnt lgkmcnt(5)
	v_mfma_f32_32x32x16_bf16 v[16:31], v[216:219], v[212:215], v[16:31]
	s_waitcnt vmcnt(15)
	ds_write_b128 v209, v[134:137] offset:64512
	global_load_dwordx4 v[88:91], v[158:159], off offset:3968
	v_mfma_f32_32x32x16_bf16 v[0:15], v[216:219], v[252:255], v[0:15]
	s_waitcnt vmcnt(15)
	ds_write_b128 v211, v[138:141] offset:13824
	global_load_dwordx4 v[92:95], v[160:161], off offset:3968
	s_setprio 0
	s_waitcnt lgkmcnt(0)
	s_barrier
	s_setprio 1
	ds_read_b128 v[212:215], v96 offset:55296
	ds_read_b128 v[216:219], v210 offset:18432
	ds_read_b128 v[220:223], v210 offset:23040
	ds_read_b128 v[224:227], v96 offset:59904
	ds_read_b128 v[228:231], v96 offset:55328
	ds_read_b128 v[244:247], v210 offset:18464
	ds_read_b128 v[252:255], v210 offset:23072
	s_waitcnt lgkmcnt(5)
	v_mfma_f32_32x32x16_bf16 v[32:47], v[212:215], v[216:219], v[32:47]
	s_waitcnt lgkmcnt(4)
	v_mfma_f32_32x32x16_bf16 v[48:63], v[212:215], v[220:223], v[48:63]
	ds_read_b128 v[212:215], v96 offset:59936
	s_waitcnt lgkmcnt(4)
	v_mfma_f32_32x32x16_bf16 v[16:31], v[224:227], v[216:219], v[16:31]
	ds_read_b128 v[216:219], v96 offset:55360
	v_mfma_f32_32x32x16_bf16 v[0:15], v[224:227], v[220:223], v[0:15]
	ds_read_b128 v[224:227], v210 offset:18496
	ds_read_b128 v[220:223], v210 offset:23104
	s_waitcnt lgkmcnt(5)
	v_mfma_f32_32x32x16_bf16 v[32:47], v[228:231], v[244:247], v[32:47]
	s_waitcnt lgkmcnt(4)
	v_mfma_f32_32x32x16_bf16 v[48:63], v[228:231], v[252:255], v[48:63]
	ds_read_b128 v[228:231], v96 offset:59968
	s_waitcnt lgkmcnt(4)
	v_mfma_f32_32x32x16_bf16 v[16:31], v[212:215], v[244:247], v[16:31]
	ds_read_b128 v[244:247], v96 offset:55392
	v_mfma_f32_32x32x16_bf16 v[0:15], v[212:215], v[252:255], v[0:15]
	ds_read_b128 v[212:215], v210 offset:18528
	ds_read_b128 v[252:255], v210 offset:23136
	s_waitcnt lgkmcnt(5)
	v_mfma_f32_32x32x16_bf16 v[32:47], v[216:219], v[224:227], v[32:47]
	s_movk_i32 s6, 0x1000
	v_add_co_u32_e32 v174, vcc, s6, v148
	s_waitcnt vmcnt(15)
	ds_write_b128 v209, v[98:101]
	s_waitcnt vmcnt(14)
	ds_write_b128 v209, v[102:105] offset:4608
	s_waitcnt lgkmcnt(6)
	v_mfma_f32_32x32x16_bf16 v[48:63], v[216:219], v[220:223], v[48:63]
	ds_read_b128 v[216:219], v96 offset:60000
	s_waitcnt vmcnt(13)
	ds_write_b128 v209, v[106:109] offset:9216
	s_waitcnt vmcnt(12)
	ds_write_b128 v209, v[110:113] offset:13824
	s_waitcnt vmcnt(11)
	ds_write_b128 v209, v[118:121] offset:36864
	s_waitcnt lgkmcnt(9)
	v_mfma_f32_32x32x16_bf16 v[16:31], v[228:231], v[224:227], v[16:31]
	s_waitcnt vmcnt(10)
	ds_write_b128 v209, v[122:125] offset:41472
	s_waitcnt vmcnt(9)
	ds_write_b128 v209, v[126:129] offset:46080
	v_mfma_f32_32x32x16_bf16 v[0:15], v[228:231], v[220:223], v[0:15]
	s_waitcnt vmcnt(8)
	ds_write_b128 v209, v[142:145] offset:50688
	v_addc_co_u32_e32 v175, vcc, 0, v149, vcc
	v_add_co_u32_e32 v176, vcc, s22, v148
	global_load_dwordx4 v[98:101], v[174:175], off
	s_nop 0
	s_waitcnt lgkmcnt(10)
	v_mfma_f32_32x32x16_bf16 v[32:47], v[244:247], v[212:215], v[32:47]
	v_addc_co_u32_e32 v177, vcc, 0, v149, vcc
	v_add_co_u32_e32 v178, vcc, s23, v148
	global_load_dwordx4 v[102:105], v[176:177], off
	s_nop 0
	v_addc_co_u32_e32 v179, vcc, 0, v149, vcc
	v_add_co_u32_e32 v180, vcc, s25, v148
	global_load_dwordx4 v[106:109], v[178:179], off
	s_waitcnt lgkmcnt(9)
	v_mfma_f32_32x32x16_bf16 v[48:63], v[244:247], v[252:255], v[48:63]
	s_nop 0
	v_addc_co_u32_e32 v181, vcc, 0, v149, vcc
	v_add_co_u32_e32 v182, vcc, s6, v146
	global_load_dwordx4 v[110:113], v[180:181], off
	s_nop 0
	v_addc_co_u32_e32 v183, vcc, 0, v147, vcc
	v_add_co_u32_e32 v184, vcc, s22, v146
	s_waitcnt lgkmcnt(6)
	v_mfma_f32_32x32x16_bf16 v[16:31], v[216:219], v[212:215], v[16:31]
	global_load_dwordx4 v[114:117], v[182:183], off
	s_nop 0
	v_addc_co_u32_e32 v185, vcc, 0, v147, vcc
	v_add_co_u32_e32 v186, vcc, s23, v146
	global_load_dwordx4 v[118:121], v[184:185], off
	s_nop 0
	v_mfma_f32_32x32x16_bf16 v[0:15], v[216:219], v[252:255], v[0:15]
	v_addc_co_u32_e32 v187, vcc, 0, v147, vcc
	v_add_co_u32_e32 v188, vcc, s25, v146
	global_load_dwordx4 v[122:125], v[186:187], off
	s_nop 0
	v_addc_co_u32_e32 v189, vcc, 0, v147, vcc
	global_load_dwordx4 v[126:129], v[188:189], off
	s_setprio 0
	s_waitcnt lgkmcnt(0)
	s_barrier
	s_setprio 1
	ds_read_b128 v[212:215], v96 offset:36864
	ds_read_b128 v[216:219], v210
	ds_read_b128 v[220:223], v210 offset:4608
	ds_read_b128 v[224:227], v96 offset:41472
	ds_read_b128 v[228:231], v96 offset:36896
	ds_read_b128 v[244:247], v210 offset:32
	ds_read_b128 v[252:255], v210 offset:4640
	s_waitcnt lgkmcnt(5)
	v_mfma_f32_32x32x16_bf16 v[32:47], v[212:215], v[216:219], v[32:47]
	s_waitcnt lgkmcnt(4)
	v_mfma_f32_32x32x16_bf16 v[48:63], v[212:215], v[220:223], v[48:63]
	ds_read_b128 v[212:215], v96 offset:41504
	s_waitcnt lgkmcnt(4)
	v_mfma_f32_32x32x16_bf16 v[16:31], v[224:227], v[216:219], v[16:31]
	ds_read_b128 v[216:219], v96 offset:36928
	v_mfma_f32_32x32x16_bf16 v[0:15], v[224:227], v[220:223], v[0:15]
	ds_read_b128 v[224:227], v210 offset:64
	ds_read_b128 v[220:223], v210 offset:4672
	s_waitcnt lgkmcnt(5)
	v_mfma_f32_32x32x16_bf16 v[32:47], v[228:231], v[244:247], v[32:47]
	s_waitcnt lgkmcnt(4)
	v_mfma_f32_32x32x16_bf16 v[48:63], v[228:231], v[252:255], v[48:63]
	ds_read_b128 v[228:231], v96 offset:41536
	s_waitcnt lgkmcnt(4)
	v_mfma_f32_32x32x16_bf16 v[16:31], v[212:215], v[244:247], v[16:31]
	ds_read_b128 v[244:247], v96 offset:36960
	v_mfma_f32_32x32x16_bf16 v[0:15], v[212:215], v[252:255], v[0:15]
	ds_read_b128 v[212:215], v210 offset:96
	ds_read_b128 v[252:255], v210 offset:4704
	s_waitcnt lgkmcnt(5)
	v_mfma_f32_32x32x16_bf16 v[32:47], v[216:219], v[224:227], v[32:47]
	s_waitcnt vmcnt(15)
	ds_write_b128 v209, v[64:67] offset:18432
	global_load_dwordx4 v[64:67], v[174:175], off offset:128
	s_waitcnt lgkmcnt(5)
	v_mfma_f32_32x32x16_bf16 v[48:63], v[216:219], v[220:223], v[48:63]
	ds_read_b128 v[216:219], v96 offset:41568
	s_waitcnt vmcnt(15)
	ds_write_b128 v209, v[68:71] offset:23040
	global_load_dwordx4 v[68:71], v[176:177], off offset:128
	s_waitcnt lgkmcnt(6)
	v_mfma_f32_32x32x16_bf16 v[16:31], v[228:231], v[224:227], v[16:31]
	s_waitcnt vmcnt(15)
	ds_write_b128 v209, v[72:75] offset:27648
	global_load_dwordx4 v[72:75], v[178:179], off offset:128
	v_mfma_f32_32x32x16_bf16 v[0:15], v[228:231], v[220:223], v[0:15]
	s_waitcnt vmcnt(15)
	ds_write_b128 v209, v[76:79] offset:32256
	global_load_dwordx4 v[76:79], v[180:181], off offset:128
	s_waitcnt lgkmcnt(6)
	v_mfma_f32_32x32x16_bf16 v[32:47], v[244:247], v[212:215], v[32:47]
	s_waitcnt vmcnt(15)
	ds_write_b128 v209, v[80:83] offset:55296
	global_load_dwordx4 v[80:83], v[182:183], off offset:128
	s_waitcnt lgkmcnt(6)
	v_mfma_f32_32x32x16_bf16 v[48:63], v[244:247], v[252:255], v[48:63]
	s_waitcnt vmcnt(15)
	ds_write_b128 v209, v[84:87] offset:59904
	global_load_dwordx4 v[84:87], v[184:185], off offset:128
	s_waitcnt lgkmcnt(5)
	v_mfma_f32_32x32x16_bf16 v[16:31], v[216:219], v[212:215], v[16:31]
	s_waitcnt vmcnt(15)
	ds_write_b128 v209, v[88:91] offset:64512
	global_load_dwordx4 v[88:91], v[186:187], off offset:128
	v_mfma_f32_32x32x16_bf16 v[0:15], v[216:219], v[252:255], v[0:15]
	s_waitcnt vmcnt(15)
	ds_write_b128 v211, v[92:95] offset:13824
	global_load_dwordx4 v[92:95], v[188:189], off offset:128
	s_setprio 0
	s_waitcnt lgkmcnt(0)
	s_barrier
	s_setprio 1
	ds_read_b128 v[212:215], v96 offset:55296
	ds_read_b128 v[216:219], v210 offset:18432
	ds_read_b128 v[220:223], v210 offset:23040
	ds_read_b128 v[224:227], v96 offset:59904
	ds_read_b128 v[228:231], v96 offset:55328
	ds_read_b128 v[244:247], v210 offset:18464
	ds_read_b128 v[252:255], v210 offset:23072
	s_waitcnt lgkmcnt(5)
	v_mfma_f32_32x32x16_bf16 v[32:47], v[212:215], v[216:219], v[32:47]
	s_waitcnt lgkmcnt(4)
	v_mfma_f32_32x32x16_bf16 v[48:63], v[212:215], v[220:223], v[48:63]
	ds_read_b128 v[212:215], v96 offset:59936
	s_waitcnt lgkmcnt(4)
	v_mfma_f32_32x32x16_bf16 v[16:31], v[224:227], v[216:219], v[16:31]
	ds_read_b128 v[216:219], v96 offset:55360
	v_mfma_f32_32x32x16_bf16 v[0:15], v[224:227], v[220:223], v[0:15]
	ds_read_b128 v[224:227], v210 offset:18496
	ds_read_b128 v[220:223], v210 offset:23104
	s_waitcnt lgkmcnt(5)
	v_mfma_f32_32x32x16_bf16 v[32:47], v[228:231], v[244:247], v[32:47]
	s_waitcnt lgkmcnt(4)
	v_mfma_f32_32x32x16_bf16 v[48:63], v[228:231], v[252:255], v[48:63]
	ds_read_b128 v[228:231], v96 offset:59968
	s_waitcnt lgkmcnt(4)
	v_mfma_f32_32x32x16_bf16 v[16:31], v[212:215], v[244:247], v[16:31]
	ds_read_b128 v[244:247], v96 offset:55392
	v_mfma_f32_32x32x16_bf16 v[0:15], v[212:215], v[252:255], v[0:15]
	ds_read_b128 v[212:215], v210 offset:18528
	ds_read_b128 v[252:255], v210 offset:23136
	s_waitcnt lgkmcnt(5)
	v_mfma_f32_32x32x16_bf16 v[32:47], v[216:219], v[224:227], v[32:47]
	s_waitcnt vmcnt(15)
	ds_write_b128 v209, v[98:101]
	global_load_dwordx4 v[98:101], v[174:175], off offset:256
	s_waitcnt lgkmcnt(5)
	v_mfma_f32_32x32x16_bf16 v[48:63], v[216:219], v[220:223], v[48:63]
	ds_read_b128 v[216:219], v96 offset:60000
	s_waitcnt vmcnt(15)
	ds_write_b128 v209, v[102:105] offset:4608
	global_load_dwordx4 v[102:105], v[176:177], off offset:256
	s_waitcnt lgkmcnt(6)
	v_mfma_f32_32x32x16_bf16 v[16:31], v[228:231], v[224:227], v[16:31]
	s_waitcnt vmcnt(15)
	ds_write_b128 v209, v[106:109] offset:9216
	global_load_dwordx4 v[106:109], v[178:179], off offset:256
	v_mfma_f32_32x32x16_bf16 v[0:15], v[228:231], v[220:223], v[0:15]
	s_waitcnt vmcnt(15)
	ds_write_b128 v209, v[110:113] offset:13824
	global_load_dwordx4 v[110:113], v[180:181], off offset:256
	s_waitcnt lgkmcnt(6)
	v_mfma_f32_32x32x16_bf16 v[32:47], v[244:247], v[212:215], v[32:47]
	s_waitcnt vmcnt(15)
	ds_write_b128 v209, v[114:117] offset:36864
	global_load_dwordx4 v[114:117], v[182:183], off offset:256
	s_waitcnt lgkmcnt(6)
	v_mfma_f32_32x32x16_bf16 v[48:63], v[244:247], v[252:255], v[48:63]
	s_waitcnt vmcnt(15)
	ds_write_b128 v209, v[118:121] offset:41472
	global_load_dwordx4 v[118:121], v[184:185], off offset:256
	s_waitcnt lgkmcnt(5)
	v_mfma_f32_32x32x16_bf16 v[16:31], v[216:219], v[212:215], v[16:31]
	s_waitcnt vmcnt(15)
	ds_write_b128 v209, v[122:125] offset:46080
	global_load_dwordx4 v[122:125], v[186:187], off offset:256
	v_mfma_f32_32x32x16_bf16 v[0:15], v[216:219], v[252:255], v[0:15]
	s_waitcnt vmcnt(15)
	ds_write_b128 v209, v[126:129] offset:50688
	global_load_dwordx4 v[126:129], v[188:189], off offset:256
	s_setprio 0
	s_waitcnt lgkmcnt(0)
	s_barrier
	s_setprio 1
	ds_read_b128 v[212:215], v96 offset:36864
	ds_read_b128 v[216:219], v210
	ds_read_b128 v[220:223], v210 offset:4608
	ds_read_b128 v[224:227], v96 offset:41472
	ds_read_b128 v[228:231], v96 offset:36896
	ds_read_b128 v[244:247], v210 offset:32
	ds_read_b128 v[252:255], v210 offset:4640
	s_waitcnt lgkmcnt(5)
	v_mfma_f32_32x32x16_bf16 v[32:47], v[212:215], v[216:219], v[32:47]
	s_waitcnt lgkmcnt(4)
	v_mfma_f32_32x32x16_bf16 v[48:63], v[212:215], v[220:223], v[48:63]
	ds_read_b128 v[212:215], v96 offset:41504
	s_waitcnt lgkmcnt(4)
	v_mfma_f32_32x32x16_bf16 v[16:31], v[224:227], v[216:219], v[16:31]
	ds_read_b128 v[216:219], v96 offset:36928
	v_mfma_f32_32x32x16_bf16 v[0:15], v[224:227], v[220:223], v[0:15]
	ds_read_b128 v[224:227], v210 offset:64
	ds_read_b128 v[220:223], v210 offset:4672
	s_waitcnt lgkmcnt(5)
	v_mfma_f32_32x32x16_bf16 v[32:47], v[228:231], v[244:247], v[32:47]
	s_waitcnt lgkmcnt(4)
	v_mfma_f32_32x32x16_bf16 v[48:63], v[228:231], v[252:255], v[48:63]
	ds_read_b128 v[228:231], v96 offset:41536
	s_waitcnt lgkmcnt(4)
	v_mfma_f32_32x32x16_bf16 v[16:31], v[212:215], v[244:247], v[16:31]
	ds_read_b128 v[244:247], v96 offset:36960
	v_mfma_f32_32x32x16_bf16 v[0:15], v[212:215], v[252:255], v[0:15]
	ds_read_b128 v[212:215], v210 offset:96
	ds_read_b128 v[252:255], v210 offset:4704
	s_waitcnt lgkmcnt(5)
	v_mfma_f32_32x32x16_bf16 v[32:47], v[216:219], v[224:227], v[32:47]
	s_waitcnt vmcnt(15)
	ds_write_b128 v209, v[64:67] offset:18432
	global_load_dwordx4 v[64:67], v[174:175], off offset:384
	s_waitcnt lgkmcnt(5)
	v_mfma_f32_32x32x16_bf16 v[48:63], v[216:219], v[220:223], v[48:63]
	ds_read_b128 v[216:219], v96 offset:41568
	s_waitcnt vmcnt(15)
	ds_write_b128 v209, v[68:71] offset:23040
	global_load_dwordx4 v[68:71], v[176:177], off offset:384
	s_waitcnt lgkmcnt(6)
	v_mfma_f32_32x32x16_bf16 v[16:31], v[228:231], v[224:227], v[16:31]
	s_waitcnt vmcnt(15)
	ds_write_b128 v209, v[72:75] offset:27648
	global_load_dwordx4 v[72:75], v[178:179], off offset:384
	v_mfma_f32_32x32x16_bf16 v[0:15], v[228:231], v[220:223], v[0:15]
	s_waitcnt vmcnt(15)
	ds_write_b128 v209, v[76:79] offset:32256
	global_load_dwordx4 v[76:79], v[180:181], off offset:384
	s_waitcnt lgkmcnt(6)
	v_mfma_f32_32x32x16_bf16 v[32:47], v[244:247], v[212:215], v[32:47]
	s_waitcnt vmcnt(15)
	ds_write_b128 v209, v[80:83] offset:55296
	global_load_dwordx4 v[80:83], v[182:183], off offset:384
	s_waitcnt lgkmcnt(6)
	v_mfma_f32_32x32x16_bf16 v[48:63], v[244:247], v[252:255], v[48:63]
	s_waitcnt vmcnt(15)
	ds_write_b128 v209, v[84:87] offset:59904
	global_load_dwordx4 v[84:87], v[184:185], off offset:384
	s_waitcnt lgkmcnt(5)
	v_mfma_f32_32x32x16_bf16 v[16:31], v[216:219], v[212:215], v[16:31]
	s_waitcnt vmcnt(15)
	ds_write_b128 v209, v[88:91] offset:64512
	global_load_dwordx4 v[88:91], v[186:187], off offset:384
	v_mfma_f32_32x32x16_bf16 v[0:15], v[216:219], v[252:255], v[0:15]
	s_waitcnt vmcnt(15)
	ds_write_b128 v211, v[92:95] offset:13824
	global_load_dwordx4 v[92:95], v[188:189], off offset:384
	s_setprio 0
	s_waitcnt lgkmcnt(0)
	s_barrier
	s_setprio 1
	ds_read_b128 v[212:215], v96 offset:55296
	ds_read_b128 v[216:219], v210 offset:18432
	ds_read_b128 v[220:223], v210 offset:23040
	ds_read_b128 v[224:227], v96 offset:59904
	ds_read_b128 v[228:231], v96 offset:55328
	ds_read_b128 v[244:247], v210 offset:18464
	ds_read_b128 v[252:255], v210 offset:23072
	s_waitcnt lgkmcnt(5)
	v_mfma_f32_32x32x16_bf16 v[32:47], v[212:215], v[216:219], v[32:47]
	s_waitcnt lgkmcnt(4)
	v_mfma_f32_32x32x16_bf16 v[48:63], v[212:215], v[220:223], v[48:63]
	ds_read_b128 v[212:215], v96 offset:59936
	s_waitcnt lgkmcnt(4)
	v_mfma_f32_32x32x16_bf16 v[16:31], v[224:227], v[216:219], v[16:31]
	ds_read_b128 v[216:219], v96 offset:55360
	v_mfma_f32_32x32x16_bf16 v[0:15], v[224:227], v[220:223], v[0:15]
	ds_read_b128 v[224:227], v210 offset:18496
	ds_read_b128 v[220:223], v210 offset:23104
	s_waitcnt lgkmcnt(5)
	v_mfma_f32_32x32x16_bf16 v[32:47], v[228:231], v[244:247], v[32:47]
	s_waitcnt lgkmcnt(4)
	v_mfma_f32_32x32x16_bf16 v[48:63], v[228:231], v[252:255], v[48:63]
	ds_read_b128 v[228:231], v96 offset:59968
	s_waitcnt lgkmcnt(4)
	v_mfma_f32_32x32x16_bf16 v[16:31], v[212:215], v[244:247], v[16:31]
	ds_read_b128 v[244:247], v96 offset:55392
	v_mfma_f32_32x32x16_bf16 v[0:15], v[212:215], v[252:255], v[0:15]
	ds_read_b128 v[212:215], v210 offset:18528
	ds_read_b128 v[252:255], v210 offset:23136
	s_waitcnt lgkmcnt(5)
	v_mfma_f32_32x32x16_bf16 v[32:47], v[216:219], v[224:227], v[32:47]
	s_waitcnt vmcnt(15)
	ds_write_b128 v209, v[98:101]
	global_load_dwordx4 v[98:101], v[174:175], off offset:512
	s_waitcnt lgkmcnt(5)
	v_mfma_f32_32x32x16_bf16 v[48:63], v[216:219], v[220:223], v[48:63]
	ds_read_b128 v[216:219], v96 offset:60000
	s_waitcnt vmcnt(15)
	ds_write_b128 v209, v[102:105] offset:4608
	global_load_dwordx4 v[102:105], v[176:177], off offset:512
	s_waitcnt lgkmcnt(6)
	v_mfma_f32_32x32x16_bf16 v[16:31], v[228:231], v[224:227], v[16:31]
	s_waitcnt vmcnt(15)
	ds_write_b128 v209, v[106:109] offset:9216
	global_load_dwordx4 v[106:109], v[178:179], off offset:512
	v_mfma_f32_32x32x16_bf16 v[0:15], v[228:231], v[220:223], v[0:15]
	s_waitcnt vmcnt(15)
	ds_write_b128 v209, v[110:113] offset:13824
	global_load_dwordx4 v[110:113], v[180:181], off offset:512
	s_waitcnt lgkmcnt(6)
	v_mfma_f32_32x32x16_bf16 v[32:47], v[244:247], v[212:215], v[32:47]
	s_waitcnt vmcnt(15)
	ds_write_b128 v209, v[114:117] offset:36864
	global_load_dwordx4 v[114:117], v[182:183], off offset:512
	s_waitcnt lgkmcnt(6)
	v_mfma_f32_32x32x16_bf16 v[48:63], v[244:247], v[252:255], v[48:63]
	s_waitcnt vmcnt(15)
	ds_write_b128 v209, v[118:121] offset:41472
	global_load_dwordx4 v[118:121], v[184:185], off offset:512
	s_waitcnt lgkmcnt(5)
	v_mfma_f32_32x32x16_bf16 v[16:31], v[216:219], v[212:215], v[16:31]
	s_waitcnt vmcnt(15)
	ds_write_b128 v209, v[122:125] offset:46080
	global_load_dwordx4 v[122:125], v[186:187], off offset:512
	v_mfma_f32_32x32x16_bf16 v[0:15], v[216:219], v[252:255], v[0:15]
	s_waitcnt vmcnt(15)
	ds_write_b128 v209, v[126:129] offset:50688
	global_load_dwordx4 v[126:129], v[188:189], off offset:512
	s_setprio 0
	s_waitcnt lgkmcnt(0)
	s_barrier
	s_setprio 1
	ds_read_b128 v[212:215], v96 offset:36864
	ds_read_b128 v[216:219], v210
	ds_read_b128 v[220:223], v210 offset:4608
	ds_read_b128 v[224:227], v96 offset:41472
	ds_read_b128 v[228:231], v96 offset:36896
	ds_read_b128 v[244:247], v210 offset:32
	ds_read_b128 v[252:255], v210 offset:4640
	s_waitcnt lgkmcnt(5)
	v_mfma_f32_32x32x16_bf16 v[32:47], v[212:215], v[216:219], v[32:47]
	s_waitcnt lgkmcnt(4)
	v_mfma_f32_32x32x16_bf16 v[48:63], v[212:215], v[220:223], v[48:63]
	ds_read_b128 v[212:215], v96 offset:41504
	s_waitcnt lgkmcnt(4)
	v_mfma_f32_32x32x16_bf16 v[16:31], v[224:227], v[216:219], v[16:31]
	ds_read_b128 v[216:219], v96 offset:36928
	v_mfma_f32_32x32x16_bf16 v[0:15], v[224:227], v[220:223], v[0:15]
	ds_read_b128 v[224:227], v210 offset:64
	ds_read_b128 v[220:223], v210 offset:4672
	s_waitcnt lgkmcnt(5)
	v_mfma_f32_32x32x16_bf16 v[32:47], v[228:231], v[244:247], v[32:47]
	s_waitcnt lgkmcnt(4)
	v_mfma_f32_32x32x16_bf16 v[48:63], v[228:231], v[252:255], v[48:63]
	ds_read_b128 v[228:231], v96 offset:41536
	s_waitcnt lgkmcnt(4)
	v_mfma_f32_32x32x16_bf16 v[16:31], v[212:215], v[244:247], v[16:31]
	ds_read_b128 v[244:247], v96 offset:36960
	v_mfma_f32_32x32x16_bf16 v[0:15], v[212:215], v[252:255], v[0:15]
	ds_read_b128 v[212:215], v210 offset:96
	ds_read_b128 v[252:255], v210 offset:4704
	s_waitcnt lgkmcnt(5)
	v_mfma_f32_32x32x16_bf16 v[32:47], v[216:219], v[224:227], v[32:47]
	s_waitcnt vmcnt(15)
	ds_write_b128 v209, v[64:67] offset:18432
	global_load_dwordx4 v[64:67], v[174:175], off offset:640
	s_waitcnt lgkmcnt(5)
	v_mfma_f32_32x32x16_bf16 v[48:63], v[216:219], v[220:223], v[48:63]
	ds_read_b128 v[216:219], v96 offset:41568
	s_waitcnt vmcnt(15)
	ds_write_b128 v209, v[68:71] offset:23040
	global_load_dwordx4 v[68:71], v[176:177], off offset:640
	s_waitcnt lgkmcnt(6)
	v_mfma_f32_32x32x16_bf16 v[16:31], v[228:231], v[224:227], v[16:31]
	s_waitcnt vmcnt(15)
	ds_write_b128 v209, v[72:75] offset:27648
	global_load_dwordx4 v[72:75], v[178:179], off offset:640
	v_mfma_f32_32x32x16_bf16 v[0:15], v[228:231], v[220:223], v[0:15]
	s_waitcnt vmcnt(15)
	ds_write_b128 v209, v[76:79] offset:32256
	global_load_dwordx4 v[76:79], v[180:181], off offset:640
	s_waitcnt lgkmcnt(6)
	v_mfma_f32_32x32x16_bf16 v[32:47], v[244:247], v[212:215], v[32:47]
	s_waitcnt vmcnt(15)
	ds_write_b128 v209, v[80:83] offset:55296
	global_load_dwordx4 v[80:83], v[182:183], off offset:640
	s_waitcnt lgkmcnt(6)
	v_mfma_f32_32x32x16_bf16 v[48:63], v[244:247], v[252:255], v[48:63]
	s_waitcnt vmcnt(15)
	ds_write_b128 v209, v[84:87] offset:59904
	global_load_dwordx4 v[84:87], v[184:185], off offset:640
	s_waitcnt lgkmcnt(5)
	v_mfma_f32_32x32x16_bf16 v[16:31], v[216:219], v[212:215], v[16:31]
	s_waitcnt vmcnt(15)
	ds_write_b128 v209, v[88:91] offset:64512
	global_load_dwordx4 v[88:91], v[186:187], off offset:640
	v_mfma_f32_32x32x16_bf16 v[0:15], v[216:219], v[252:255], v[0:15]
	s_waitcnt vmcnt(15)
	ds_write_b128 v211, v[92:95] offset:13824
	global_load_dwordx4 v[92:95], v[188:189], off offset:640
	s_setprio 0
	s_waitcnt lgkmcnt(0)
	s_barrier
	s_setprio 1
	ds_read_b128 v[212:215], v96 offset:55296
	ds_read_b128 v[216:219], v210 offset:18432
	ds_read_b128 v[220:223], v210 offset:23040
	ds_read_b128 v[224:227], v96 offset:59904
	ds_read_b128 v[228:231], v96 offset:55328
	ds_read_b128 v[244:247], v210 offset:18464
	ds_read_b128 v[252:255], v210 offset:23072
	s_waitcnt lgkmcnt(5)
	v_mfma_f32_32x32x16_bf16 v[32:47], v[212:215], v[216:219], v[32:47]
	s_waitcnt lgkmcnt(4)
	v_mfma_f32_32x32x16_bf16 v[48:63], v[212:215], v[220:223], v[48:63]
	ds_read_b128 v[212:215], v96 offset:59936
	s_waitcnt lgkmcnt(4)
	v_mfma_f32_32x32x16_bf16 v[16:31], v[224:227], v[216:219], v[16:31]
	ds_read_b128 v[216:219], v96 offset:55360
	v_mfma_f32_32x32x16_bf16 v[0:15], v[224:227], v[220:223], v[0:15]
	ds_read_b128 v[224:227], v210 offset:18496
	ds_read_b128 v[220:223], v210 offset:23104
	s_waitcnt lgkmcnt(5)
	v_mfma_f32_32x32x16_bf16 v[32:47], v[228:231], v[244:247], v[32:47]
	s_waitcnt lgkmcnt(4)
	v_mfma_f32_32x32x16_bf16 v[48:63], v[228:231], v[252:255], v[48:63]
	ds_read_b128 v[228:231], v96 offset:59968
	s_waitcnt lgkmcnt(4)
	v_mfma_f32_32x32x16_bf16 v[16:31], v[212:215], v[244:247], v[16:31]
	ds_read_b128 v[244:247], v96 offset:55392
	v_mfma_f32_32x32x16_bf16 v[0:15], v[212:215], v[252:255], v[0:15]
	ds_read_b128 v[212:215], v210 offset:18528
	ds_read_b128 v[252:255], v210 offset:23136
	s_waitcnt lgkmcnt(5)
	v_mfma_f32_32x32x16_bf16 v[32:47], v[216:219], v[224:227], v[32:47]
	s_waitcnt vmcnt(15)
	ds_write_b128 v209, v[98:101]
	global_load_dwordx4 v[98:101], v[174:175], off offset:768
	s_waitcnt lgkmcnt(5)
	v_mfma_f32_32x32x16_bf16 v[48:63], v[216:219], v[220:223], v[48:63]
	ds_read_b128 v[216:219], v96 offset:60000
	s_waitcnt vmcnt(15)
	ds_write_b128 v209, v[102:105] offset:4608
	global_load_dwordx4 v[102:105], v[176:177], off offset:768
	s_waitcnt lgkmcnt(6)
	v_mfma_f32_32x32x16_bf16 v[16:31], v[228:231], v[224:227], v[16:31]
	s_waitcnt vmcnt(15)
	ds_write_b128 v209, v[106:109] offset:9216
	global_load_dwordx4 v[106:109], v[178:179], off offset:768
	v_mfma_f32_32x32x16_bf16 v[0:15], v[228:231], v[220:223], v[0:15]
	s_waitcnt vmcnt(15)
	ds_write_b128 v209, v[110:113] offset:13824
	global_load_dwordx4 v[110:113], v[180:181], off offset:768
	s_waitcnt lgkmcnt(6)
	v_mfma_f32_32x32x16_bf16 v[32:47], v[244:247], v[212:215], v[32:47]
	s_waitcnt vmcnt(15)
	ds_write_b128 v209, v[114:117] offset:36864
	global_load_dwordx4 v[114:117], v[182:183], off offset:768
	s_waitcnt lgkmcnt(6)
	v_mfma_f32_32x32x16_bf16 v[48:63], v[244:247], v[252:255], v[48:63]
	s_waitcnt vmcnt(15)
	ds_write_b128 v209, v[118:121] offset:41472
	global_load_dwordx4 v[118:121], v[184:185], off offset:768
	s_waitcnt lgkmcnt(5)
	v_mfma_f32_32x32x16_bf16 v[16:31], v[216:219], v[212:215], v[16:31]
	s_waitcnt vmcnt(15)
	ds_write_b128 v209, v[122:125] offset:46080
	global_load_dwordx4 v[122:125], v[186:187], off offset:768
	v_mfma_f32_32x32x16_bf16 v[0:15], v[216:219], v[252:255], v[0:15]
	s_waitcnt vmcnt(15)
	ds_write_b128 v209, v[126:129] offset:50688
	global_load_dwordx4 v[126:129], v[188:189], off offset:768
	s_setprio 0
	s_waitcnt lgkmcnt(0)
	s_barrier
	s_setprio 1
	ds_read_b128 v[212:215], v96 offset:36864
	ds_read_b128 v[216:219], v210
	ds_read_b128 v[220:223], v210 offset:4608
	ds_read_b128 v[224:227], v96 offset:41472
	ds_read_b128 v[228:231], v96 offset:36896
	ds_read_b128 v[244:247], v210 offset:32
	ds_read_b128 v[252:255], v210 offset:4640
	s_waitcnt lgkmcnt(5)
	v_mfma_f32_32x32x16_bf16 v[32:47], v[212:215], v[216:219], v[32:47]
	s_waitcnt lgkmcnt(4)
	v_mfma_f32_32x32x16_bf16 v[48:63], v[212:215], v[220:223], v[48:63]
	ds_read_b128 v[212:215], v96 offset:41504
	s_waitcnt lgkmcnt(4)
	v_mfma_f32_32x32x16_bf16 v[16:31], v[224:227], v[216:219], v[16:31]
	ds_read_b128 v[216:219], v96 offset:36928
	v_mfma_f32_32x32x16_bf16 v[0:15], v[224:227], v[220:223], v[0:15]
	ds_read_b128 v[224:227], v210 offset:64
	ds_read_b128 v[220:223], v210 offset:4672
	s_waitcnt lgkmcnt(5)
	v_mfma_f32_32x32x16_bf16 v[32:47], v[228:231], v[244:247], v[32:47]
	s_waitcnt lgkmcnt(4)
	v_mfma_f32_32x32x16_bf16 v[48:63], v[228:231], v[252:255], v[48:63]
	ds_read_b128 v[228:231], v96 offset:41536
	s_waitcnt lgkmcnt(4)
	v_mfma_f32_32x32x16_bf16 v[16:31], v[212:215], v[244:247], v[16:31]
	ds_read_b128 v[244:247], v96 offset:36960
	v_mfma_f32_32x32x16_bf16 v[0:15], v[212:215], v[252:255], v[0:15]
	ds_read_b128 v[212:215], v210 offset:96
	ds_read_b128 v[252:255], v210 offset:4704
	s_waitcnt lgkmcnt(5)
	v_mfma_f32_32x32x16_bf16 v[32:47], v[216:219], v[224:227], v[32:47]
	s_waitcnt vmcnt(15)
	ds_write_b128 v209, v[64:67] offset:18432
	global_load_dwordx4 v[64:67], v[174:175], off offset:896
	s_waitcnt lgkmcnt(5)
	v_mfma_f32_32x32x16_bf16 v[48:63], v[216:219], v[220:223], v[48:63]
	ds_read_b128 v[216:219], v96 offset:41568
	s_waitcnt vmcnt(15)
	ds_write_b128 v209, v[68:71] offset:23040
	global_load_dwordx4 v[68:71], v[176:177], off offset:896
	s_waitcnt lgkmcnt(6)
	v_mfma_f32_32x32x16_bf16 v[16:31], v[228:231], v[224:227], v[16:31]
	s_waitcnt vmcnt(15)
	ds_write_b128 v209, v[72:75] offset:27648
	global_load_dwordx4 v[72:75], v[178:179], off offset:896
	v_mfma_f32_32x32x16_bf16 v[0:15], v[228:231], v[220:223], v[0:15]
	s_waitcnt vmcnt(15)
	ds_write_b128 v209, v[76:79] offset:32256
	global_load_dwordx4 v[76:79], v[180:181], off offset:896
	s_waitcnt lgkmcnt(6)
	v_mfma_f32_32x32x16_bf16 v[32:47], v[244:247], v[212:215], v[32:47]
	s_waitcnt vmcnt(15)
	ds_write_b128 v209, v[80:83] offset:55296
	global_load_dwordx4 v[80:83], v[182:183], off offset:896
	s_waitcnt lgkmcnt(6)
	v_mfma_f32_32x32x16_bf16 v[48:63], v[244:247], v[252:255], v[48:63]
	s_waitcnt vmcnt(15)
	ds_write_b128 v209, v[84:87] offset:59904
	global_load_dwordx4 v[84:87], v[184:185], off offset:896
	s_waitcnt lgkmcnt(5)
	v_mfma_f32_32x32x16_bf16 v[16:31], v[216:219], v[212:215], v[16:31]
	s_waitcnt vmcnt(15)
	ds_write_b128 v209, v[88:91] offset:64512
	global_load_dwordx4 v[88:91], v[186:187], off offset:896
	v_mfma_f32_32x32x16_bf16 v[0:15], v[216:219], v[252:255], v[0:15]
	s_waitcnt vmcnt(15)
	ds_write_b128 v211, v[92:95] offset:13824
	global_load_dwordx4 v[92:95], v[188:189], off offset:896
	s_setprio 0
	s_waitcnt lgkmcnt(0)
	s_barrier
	s_setprio 1
	ds_read_b128 v[212:215], v96 offset:55296
	ds_read_b128 v[216:219], v210 offset:18432
	ds_read_b128 v[220:223], v210 offset:23040
	ds_read_b128 v[224:227], v96 offset:59904
	ds_read_b128 v[228:231], v96 offset:55328
	ds_read_b128 v[244:247], v210 offset:18464
	ds_read_b128 v[252:255], v210 offset:23072
	s_waitcnt lgkmcnt(5)
	v_mfma_f32_32x32x16_bf16 v[32:47], v[212:215], v[216:219], v[32:47]
	s_waitcnt lgkmcnt(4)
	v_mfma_f32_32x32x16_bf16 v[48:63], v[212:215], v[220:223], v[48:63]
	ds_read_b128 v[212:215], v96 offset:59936
	s_waitcnt lgkmcnt(4)
	v_mfma_f32_32x32x16_bf16 v[16:31], v[224:227], v[216:219], v[16:31]
	ds_read_b128 v[216:219], v96 offset:55360
	v_mfma_f32_32x32x16_bf16 v[0:15], v[224:227], v[220:223], v[0:15]
	ds_read_b128 v[224:227], v210 offset:18496
	ds_read_b128 v[220:223], v210 offset:23104
	s_waitcnt lgkmcnt(5)
	v_mfma_f32_32x32x16_bf16 v[32:47], v[228:231], v[244:247], v[32:47]
	s_waitcnt lgkmcnt(4)
	v_mfma_f32_32x32x16_bf16 v[48:63], v[228:231], v[252:255], v[48:63]
	ds_read_b128 v[228:231], v96 offset:59968
	s_waitcnt lgkmcnt(4)
	v_mfma_f32_32x32x16_bf16 v[16:31], v[212:215], v[244:247], v[16:31]
	ds_read_b128 v[244:247], v96 offset:55392
	v_mfma_f32_32x32x16_bf16 v[0:15], v[212:215], v[252:255], v[0:15]
	ds_read_b128 v[212:215], v210 offset:18528
	ds_read_b128 v[252:255], v210 offset:23136
	s_waitcnt lgkmcnt(5)
	v_mfma_f32_32x32x16_bf16 v[32:47], v[216:219], v[224:227], v[32:47]
	s_waitcnt vmcnt(15)
	ds_write_b128 v209, v[98:101]
	global_load_dwordx4 v[98:101], v[174:175], off offset:1024
	s_waitcnt lgkmcnt(5)
	v_mfma_f32_32x32x16_bf16 v[48:63], v[216:219], v[220:223], v[48:63]
	ds_read_b128 v[216:219], v96 offset:60000
	s_waitcnt vmcnt(15)
	ds_write_b128 v209, v[102:105] offset:4608
	global_load_dwordx4 v[102:105], v[176:177], off offset:1024
	s_waitcnt lgkmcnt(6)
	v_mfma_f32_32x32x16_bf16 v[16:31], v[228:231], v[224:227], v[16:31]
	s_waitcnt vmcnt(15)
	ds_write_b128 v209, v[106:109] offset:9216
	global_load_dwordx4 v[106:109], v[178:179], off offset:1024
	v_mfma_f32_32x32x16_bf16 v[0:15], v[228:231], v[220:223], v[0:15]
	s_waitcnt vmcnt(15)
	ds_write_b128 v209, v[110:113] offset:13824
	global_load_dwordx4 v[110:113], v[180:181], off offset:1024
	s_waitcnt lgkmcnt(6)
	v_mfma_f32_32x32x16_bf16 v[32:47], v[244:247], v[212:215], v[32:47]
	s_waitcnt vmcnt(15)
	ds_write_b128 v209, v[114:117] offset:36864
	global_load_dwordx4 v[114:117], v[182:183], off offset:1024
	s_waitcnt lgkmcnt(6)
	v_mfma_f32_32x32x16_bf16 v[48:63], v[244:247], v[252:255], v[48:63]
	s_waitcnt vmcnt(15)
	ds_write_b128 v209, v[118:121] offset:41472
	global_load_dwordx4 v[118:121], v[184:185], off offset:1024
	s_waitcnt lgkmcnt(5)
	v_mfma_f32_32x32x16_bf16 v[16:31], v[216:219], v[212:215], v[16:31]
	s_waitcnt vmcnt(15)
	ds_write_b128 v209, v[122:125] offset:46080
	global_load_dwordx4 v[122:125], v[186:187], off offset:1024
	v_mfma_f32_32x32x16_bf16 v[0:15], v[216:219], v[252:255], v[0:15]
	s_waitcnt vmcnt(15)
	ds_write_b128 v209, v[126:129] offset:50688
	global_load_dwordx4 v[126:129], v[188:189], off offset:1024
	s_setprio 0
	s_waitcnt lgkmcnt(0)
	s_barrier
	s_setprio 1
	ds_read_b128 v[212:215], v96 offset:36864
	ds_read_b128 v[216:219], v210
	ds_read_b128 v[220:223], v210 offset:4608
	ds_read_b128 v[224:227], v96 offset:41472
	ds_read_b128 v[228:231], v96 offset:36896
	ds_read_b128 v[244:247], v210 offset:32
	ds_read_b128 v[252:255], v210 offset:4640
	s_waitcnt lgkmcnt(5)
	v_mfma_f32_32x32x16_bf16 v[32:47], v[212:215], v[216:219], v[32:47]
	s_waitcnt lgkmcnt(4)
	v_mfma_f32_32x32x16_bf16 v[48:63], v[212:215], v[220:223], v[48:63]
	ds_read_b128 v[212:215], v96 offset:41504
	s_waitcnt lgkmcnt(4)
	v_mfma_f32_32x32x16_bf16 v[16:31], v[224:227], v[216:219], v[16:31]
	ds_read_b128 v[216:219], v96 offset:36928
	v_mfma_f32_32x32x16_bf16 v[0:15], v[224:227], v[220:223], v[0:15]
	ds_read_b128 v[224:227], v210 offset:64
	ds_read_b128 v[220:223], v210 offset:4672
	s_waitcnt lgkmcnt(5)
	v_mfma_f32_32x32x16_bf16 v[32:47], v[228:231], v[244:247], v[32:47]
	s_waitcnt lgkmcnt(4)
	v_mfma_f32_32x32x16_bf16 v[48:63], v[228:231], v[252:255], v[48:63]
	ds_read_b128 v[228:231], v96 offset:41536
	s_waitcnt lgkmcnt(4)
	v_mfma_f32_32x32x16_bf16 v[16:31], v[212:215], v[244:247], v[16:31]
	ds_read_b128 v[244:247], v96 offset:36960
	v_mfma_f32_32x32x16_bf16 v[0:15], v[212:215], v[252:255], v[0:15]
	ds_read_b128 v[212:215], v210 offset:96
	ds_read_b128 v[252:255], v210 offset:4704
	s_waitcnt lgkmcnt(5)
	v_mfma_f32_32x32x16_bf16 v[32:47], v[216:219], v[224:227], v[32:47]
	s_waitcnt vmcnt(15)
	ds_write_b128 v209, v[64:67] offset:18432
	global_load_dwordx4 v[130:133], v[174:175], off offset:1152
	s_waitcnt lgkmcnt(5)
	v_mfma_f32_32x32x16_bf16 v[48:63], v[216:219], v[220:223], v[48:63]
	ds_read_b128 v[216:219], v96 offset:41568
	s_waitcnt vmcnt(15)
	ds_write_b128 v209, v[68:71] offset:23040
	global_load_dwordx4 v[134:137], v[176:177], off offset:1152
	s_waitcnt lgkmcnt(6)
	v_mfma_f32_32x32x16_bf16 v[16:31], v[228:231], v[224:227], v[16:31]
	s_waitcnt vmcnt(15)
	ds_write_b128 v209, v[72:75] offset:27648
	global_load_dwordx4 v[138:141], v[178:179], off offset:1152
	v_mfma_f32_32x32x16_bf16 v[0:15], v[228:231], v[220:223], v[0:15]
	s_waitcnt vmcnt(15)
	ds_write_b128 v209, v[76:79] offset:32256
	global_load_dwordx4 v[142:145], v[180:181], off offset:1152
	s_waitcnt lgkmcnt(6)
	v_mfma_f32_32x32x16_bf16 v[32:47], v[244:247], v[212:215], v[32:47]
	s_waitcnt vmcnt(15)
	ds_write_b128 v209, v[80:83] offset:55296
	global_load_dwordx4 v[146:149], v[182:183], off offset:1152
	s_waitcnt lgkmcnt(6)
	v_mfma_f32_32x32x16_bf16 v[48:63], v[244:247], v[252:255], v[48:63]
	s_waitcnt vmcnt(15)
	ds_write_b128 v209, v[84:87] offset:59904
	global_load_dwordx4 v[150:153], v[184:185], off offset:1152
	s_waitcnt lgkmcnt(5)
	v_mfma_f32_32x32x16_bf16 v[16:31], v[216:219], v[212:215], v[16:31]
	s_waitcnt vmcnt(15)
	ds_write_b128 v209, v[88:91] offset:64512
	global_load_dwordx4 v[154:157], v[186:187], off offset:1152
	v_mfma_f32_32x32x16_bf16 v[0:15], v[216:219], v[252:255], v[0:15]
	s_waitcnt vmcnt(15)
	ds_write_b128 v211, v[92:95] offset:13824
	global_load_dwordx4 v[158:161], v[188:189], off offset:1152
	s_setprio 0
	s_waitcnt lgkmcnt(0)
	s_barrier
	s_setprio 1
	ds_read_b128 v[212:215], v96 offset:55296
	ds_read_b128 v[216:219], v210 offset:18432
	ds_read_b128 v[220:223], v210 offset:23040
	ds_read_b128 v[224:227], v96 offset:59904
	ds_read_b128 v[228:231], v96 offset:55328
	ds_read_b128 v[244:247], v210 offset:18464
	ds_read_b128 v[252:255], v210 offset:23072
	s_waitcnt lgkmcnt(5)
	v_mfma_f32_32x32x16_bf16 v[32:47], v[212:215], v[216:219], v[32:47]
	s_waitcnt lgkmcnt(4)
	v_mfma_f32_32x32x16_bf16 v[48:63], v[212:215], v[220:223], v[48:63]
	ds_read_b128 v[212:215], v96 offset:59936
	s_waitcnt lgkmcnt(4)
	v_mfma_f32_32x32x16_bf16 v[16:31], v[224:227], v[216:219], v[16:31]
	ds_read_b128 v[216:219], v96 offset:55360
	v_mfma_f32_32x32x16_bf16 v[0:15], v[224:227], v[220:223], v[0:15]
	ds_read_b128 v[224:227], v210 offset:18496
	ds_read_b128 v[220:223], v210 offset:23104
	s_waitcnt lgkmcnt(5)
	v_mfma_f32_32x32x16_bf16 v[32:47], v[228:231], v[244:247], v[32:47]
	s_waitcnt lgkmcnt(4)
	v_mfma_f32_32x32x16_bf16 v[48:63], v[228:231], v[252:255], v[48:63]
	ds_read_b128 v[228:231], v96 offset:59968
	s_waitcnt lgkmcnt(4)
	v_mfma_f32_32x32x16_bf16 v[16:31], v[212:215], v[244:247], v[16:31]
	ds_read_b128 v[244:247], v96 offset:55392
	v_mfma_f32_32x32x16_bf16 v[0:15], v[212:215], v[252:255], v[0:15]
	ds_read_b128 v[212:215], v210 offset:18528
	ds_read_b128 v[252:255], v210 offset:23136
	s_waitcnt lgkmcnt(5)
	v_mfma_f32_32x32x16_bf16 v[32:47], v[216:219], v[224:227], v[32:47]
	s_waitcnt vmcnt(15)
	ds_write_b128 v209, v[98:101]
	global_load_dwordx4 v[64:67], v[174:175], off offset:1280
	s_waitcnt lgkmcnt(5)
	v_mfma_f32_32x32x16_bf16 v[48:63], v[216:219], v[220:223], v[48:63]
	ds_read_b128 v[216:219], v96 offset:60000
	s_waitcnt vmcnt(15)
	ds_write_b128 v209, v[102:105] offset:4608
	global_load_dwordx4 v[68:71], v[176:177], off offset:1280
	s_waitcnt lgkmcnt(6)
	v_mfma_f32_32x32x16_bf16 v[16:31], v[228:231], v[224:227], v[16:31]
	s_waitcnt vmcnt(15)
	ds_write_b128 v209, v[106:109] offset:9216
	global_load_dwordx4 v[72:75], v[178:179], off offset:1280
	v_mfma_f32_32x32x16_bf16 v[0:15], v[228:231], v[220:223], v[0:15]
	s_waitcnt vmcnt(15)
	ds_write_b128 v209, v[110:113] offset:13824
	global_load_dwordx4 v[76:79], v[180:181], off offset:1280
	s_waitcnt lgkmcnt(6)
	v_mfma_f32_32x32x16_bf16 v[32:47], v[244:247], v[212:215], v[32:47]
	s_waitcnt vmcnt(15)
	ds_write_b128 v209, v[114:117] offset:36864
	global_load_dwordx4 v[80:83], v[182:183], off offset:1280
	s_waitcnt lgkmcnt(6)
	v_mfma_f32_32x32x16_bf16 v[48:63], v[244:247], v[252:255], v[48:63]
	s_waitcnt vmcnt(15)
	ds_write_b128 v209, v[118:121] offset:41472
	global_load_dwordx4 v[84:87], v[184:185], off offset:1280
	s_waitcnt lgkmcnt(5)
	v_mfma_f32_32x32x16_bf16 v[16:31], v[216:219], v[212:215], v[16:31]
	s_waitcnt vmcnt(15)
	ds_write_b128 v209, v[122:125] offset:46080
	global_load_dwordx4 v[88:91], v[186:187], off offset:1280
	v_mfma_f32_32x32x16_bf16 v[0:15], v[216:219], v[252:255], v[0:15]
	s_waitcnt vmcnt(15)
	ds_write_b128 v209, v[126:129] offset:50688
	global_load_dwordx4 v[92:95], v[188:189], off offset:1280
	s_setprio 0
	s_waitcnt lgkmcnt(0)
	s_barrier
	s_setprio 1
	ds_read_b128 v[212:215], v96 offset:36864
	ds_read_b128 v[216:219], v210
	ds_read_b128 v[220:223], v210 offset:4608
	ds_read_b128 v[224:227], v96 offset:41472
	ds_read_b128 v[228:231], v96 offset:36896
	ds_read_b128 v[244:247], v210 offset:32
	ds_read_b128 v[252:255], v210 offset:4640
	s_waitcnt lgkmcnt(5)
	v_mfma_f32_32x32x16_bf16 v[32:47], v[212:215], v[216:219], v[32:47]
	s_waitcnt lgkmcnt(4)
	v_mfma_f32_32x32x16_bf16 v[48:63], v[212:215], v[220:223], v[48:63]
	ds_read_b128 v[212:215], v96 offset:41504
	s_waitcnt lgkmcnt(4)
	v_mfma_f32_32x32x16_bf16 v[16:31], v[224:227], v[216:219], v[16:31]
	ds_read_b128 v[216:219], v96 offset:36928
	v_mfma_f32_32x32x16_bf16 v[0:15], v[224:227], v[220:223], v[0:15]
	ds_read_b128 v[224:227], v210 offset:64
	ds_read_b128 v[220:223], v210 offset:4672
	s_waitcnt lgkmcnt(5)
	v_mfma_f32_32x32x16_bf16 v[32:47], v[228:231], v[244:247], v[32:47]
	s_waitcnt lgkmcnt(4)
	v_mfma_f32_32x32x16_bf16 v[48:63], v[228:231], v[252:255], v[48:63]
	ds_read_b128 v[228:231], v96 offset:41536
	s_waitcnt lgkmcnt(4)
	v_mfma_f32_32x32x16_bf16 v[16:31], v[212:215], v[244:247], v[16:31]
	ds_read_b128 v[244:247], v96 offset:36960
	v_mfma_f32_32x32x16_bf16 v[0:15], v[212:215], v[252:255], v[0:15]
	ds_read_b128 v[212:215], v210 offset:96
	ds_read_b128 v[252:255], v210 offset:4704
	s_waitcnt lgkmcnt(5)
	v_mfma_f32_32x32x16_bf16 v[32:47], v[216:219], v[224:227], v[32:47]
	s_waitcnt vmcnt(15)
	ds_write_b128 v209, v[130:133] offset:18432
	global_load_dwordx4 v[100:103], v[174:175], off offset:1408
	s_waitcnt lgkmcnt(5)
	v_mfma_f32_32x32x16_bf16 v[48:63], v[216:219], v[220:223], v[48:63]
	ds_read_b128 v[216:219], v96 offset:41568
	s_waitcnt vmcnt(15)
	ds_write_b128 v209, v[134:137] offset:23040
	global_load_dwordx4 v[104:107], v[176:177], off offset:1408
	s_waitcnt lgkmcnt(6)
	v_mfma_f32_32x32x16_bf16 v[16:31], v[228:231], v[224:227], v[16:31]
	s_waitcnt vmcnt(15)
	ds_write_b128 v209, v[138:141] offset:27648
	global_load_dwordx4 v[112:115], v[178:179], off offset:1408
	v_mfma_f32_32x32x16_bf16 v[0:15], v[228:231], v[220:223], v[0:15]
	s_waitcnt vmcnt(15)
	ds_write_b128 v209, v[142:145] offset:32256
	global_load_dwordx4 v[108:111], v[180:181], off offset:1408
	s_waitcnt lgkmcnt(6)
	v_mfma_f32_32x32x16_bf16 v[32:47], v[244:247], v[212:215], v[32:47]
	s_waitcnt vmcnt(15)
	ds_write_b128 v209, v[146:149] offset:55296
	global_load_dwordx4 v[116:119], v[182:183], off offset:1408
	s_waitcnt lgkmcnt(6)
	v_mfma_f32_32x32x16_bf16 v[48:63], v[244:247], v[252:255], v[48:63]
	s_waitcnt vmcnt(15)
	ds_write_b128 v209, v[150:153] offset:59904
	global_load_dwordx4 v[124:127], v[184:185], off offset:1408
	s_waitcnt lgkmcnt(5)
	v_mfma_f32_32x32x16_bf16 v[16:31], v[216:219], v[212:215], v[16:31]
	s_waitcnt vmcnt(15)
	ds_write_b128 v209, v[154:157] offset:64512
	global_load_dwordx4 v[120:123], v[186:187], off offset:1408
	v_mfma_f32_32x32x16_bf16 v[0:15], v[216:219], v[252:255], v[0:15]
	s_waitcnt vmcnt(15)
	ds_write_b128 v211, v[158:161] offset:13824
	global_load_dwordx4 v[128:131], v[188:189], off offset:1408
	s_setprio 0
	s_waitcnt lgkmcnt(0)
	s_barrier
	s_setprio 1
	ds_read_b128 v[212:215], v96 offset:55296
	ds_read_b128 v[216:219], v210 offset:18432
	ds_read_b128 v[220:223], v210 offset:23040
	ds_read_b128 v[224:227], v96 offset:59904
	ds_read_b128 v[228:231], v96 offset:55328
	ds_read_b128 v[244:247], v210 offset:18464
	ds_read_b128 v[252:255], v210 offset:23072
	s_waitcnt lgkmcnt(5)
	v_mfma_f32_32x32x16_bf16 v[32:47], v[212:215], v[216:219], v[32:47]
	s_waitcnt lgkmcnt(4)
	v_mfma_f32_32x32x16_bf16 v[48:63], v[212:215], v[220:223], v[48:63]
	ds_read_b128 v[212:215], v96 offset:59936
	s_waitcnt lgkmcnt(4)
	v_mfma_f32_32x32x16_bf16 v[16:31], v[224:227], v[216:219], v[16:31]
	ds_read_b128 v[216:219], v96 offset:55360
	v_mfma_f32_32x32x16_bf16 v[0:15], v[224:227], v[220:223], v[0:15]
	ds_read_b128 v[224:227], v210 offset:18496
	ds_read_b128 v[220:223], v210 offset:23104
	s_waitcnt lgkmcnt(5)
	v_mfma_f32_32x32x16_bf16 v[32:47], v[228:231], v[244:247], v[32:47]
	s_waitcnt lgkmcnt(4)
	v_mfma_f32_32x32x16_bf16 v[48:63], v[228:231], v[252:255], v[48:63]
	ds_read_b128 v[228:231], v96 offset:59968
	s_waitcnt lgkmcnt(4)
	v_mfma_f32_32x32x16_bf16 v[16:31], v[212:215], v[244:247], v[16:31]
	ds_read_b128 v[244:247], v96 offset:55392
	v_mfma_f32_32x32x16_bf16 v[0:15], v[212:215], v[252:255], v[0:15]
	ds_read_b128 v[212:215], v210 offset:18528
	ds_read_b128 v[252:255], v210 offset:23136
	s_waitcnt lgkmcnt(5)
	v_mfma_f32_32x32x16_bf16 v[32:47], v[216:219], v[224:227], v[32:47]
	s_waitcnt lgkmcnt(4)
	v_mfma_f32_32x32x16_bf16 v[48:63], v[216:219], v[220:223], v[48:63]
	ds_read_b128 v[216:219], v96 offset:60000
	s_waitcnt lgkmcnt(4)
	v_mfma_f32_32x32x16_bf16 v[16:31], v[228:231], v[224:227], v[16:31]
	v_mfma_f32_32x32x16_bf16 v[0:15], v[228:231], v[220:223], v[0:15]
	s_waitcnt lgkmcnt(2)
	v_mfma_f32_32x32x16_bf16 v[32:47], v[244:247], v[212:215], v[32:47]
	s_waitcnt lgkmcnt(1)
	v_mfma_f32_32x32x16_bf16 v[48:63], v[244:247], v[252:255], v[48:63]
	s_waitcnt lgkmcnt(0)
	v_mfma_f32_32x32x16_bf16 v[16:31], v[216:219], v[212:215], v[16:31]
	v_mfma_f32_32x32x16_bf16 v[0:15], v[216:219], v[252:255], v[0:15]
	s_setprio 0
	v_cndmask_b32_e64 v98, 0, 1, s[2:3]
	v_cmp_ne_u32_e64 s[38:39], 1, v98
	s_andn2_b64 vcc, exec, s[2:3]
	s_waitcnt vmcnt(15)
	ds_write_b128 v209, v[64:67]
	s_waitcnt vmcnt(14)
	ds_write_b128 v209, v[68:71] offset:4608
	s_waitcnt vmcnt(13)
	ds_write_b128 v209, v[72:75] offset:9216
	s_waitcnt vmcnt(12)
	ds_write_b128 v209, v[76:79] offset:13824
	s_waitcnt vmcnt(11)
	ds_write_b128 v209, v[80:83] offset:36864
	s_waitcnt vmcnt(10)
	ds_write_b128 v209, v[84:87] offset:41472
	s_waitcnt vmcnt(9)
	ds_write_b128 v209, v[88:91] offset:46080
	s_waitcnt vmcnt(8)
	ds_write_b128 v209, v[92:95] offset:50688
	s_cbranch_vccnz .LBB0_332
	v_add_co_u32_e32 v68, vcc, 0x2c000, v172
	global_load_dwordx4 v[64:67], v[172:173], off
	s_nop 0
	v_addc_co_u32_e32 v69, vcc, 0, v173, vcc
	v_add_co_u32_e32 v72, vcc, 0x58000, v172
	s_nop 1
	v_addc_co_u32_e32 v73, vcc, 0, v173, vcc
	v_add_co_u32_e32 v76, vcc, 0x84000, v172
	global_load_dwordx4 v[68:71], v[68:69], off
	global_load_dwordx4 v[72:75], v[72:73], off
	v_addc_co_u32_e32 v77, vcc, 0, v173, vcc
	v_add_co_u32_e32 v84, vcc, 0x2c000, v170
	global_load_dwordx4 v[76:79], v[76:77], off
	s_nop 0
	global_load_dwordx4 v[80:83], v[170:171], off
	v_addc_co_u32_e32 v85, vcc, 0, v171, vcc
	v_add_co_u32_e32 v88, vcc, 0x58000, v170
	s_nop 1
	v_addc_co_u32_e32 v89, vcc, 0, v171, vcc
	v_add_co_u32_e32 v92, vcc, 0x84000, v170
	global_load_dwordx4 v[84:87], v[84:85], off
	s_nop 0
	global_load_dwordx4 v[88:91], v[88:89], off
	v_addc_co_u32_e32 v93, vcc, 0, v171, vcc
	global_load_dwordx4 v[92:95], v[92:93], off

.LBB0_334:
	s_waitcnt lgkmcnt(0)
	s_barrier
	s_setprio 1
	ds_read_b128 v[212:215], v96 offset:55296
	ds_read_b128 v[216:219], v210 offset:18432
	ds_read_b128 v[220:223], v210 offset:23040
	ds_read_b128 v[224:227], v96 offset:59904
	ds_read_b128 v[228:231], v96 offset:55328
	ds_read_b128 v[244:247], v210 offset:18464
	ds_read_b128 v[252:255], v210 offset:23072
	s_waitcnt lgkmcnt(5)
	v_mfma_f32_32x32x16_bf16 v[32:47], v[212:215], v[216:219], v[32:47]
	s_waitcnt lgkmcnt(4)
	v_mfma_f32_32x32x16_bf16 v[48:63], v[212:215], v[220:223], v[48:63]
	ds_read_b128 v[212:215], v96 offset:59936
	s_waitcnt lgkmcnt(4)
	v_mfma_f32_32x32x16_bf16 v[16:31], v[224:227], v[216:219], v[16:31]
	ds_read_b128 v[216:219], v96 offset:55360
	v_mfma_f32_32x32x16_bf16 v[0:15], v[224:227], v[220:223], v[0:15]
	ds_read_b128 v[224:227], v210 offset:18496
	ds_read_b128 v[220:223], v210 offset:23104
	s_waitcnt lgkmcnt(5)
	v_mfma_f32_32x32x16_bf16 v[32:47], v[228:231], v[244:247], v[32:47]
	s_waitcnt lgkmcnt(4)
	v_mfma_f32_32x32x16_bf16 v[48:63], v[228:231], v[252:255], v[48:63]
	ds_read_b128 v[228:231], v96 offset:59968
	s_waitcnt lgkmcnt(4)
	v_mfma_f32_32x32x16_bf16 v[16:31], v[212:215], v[244:247], v[16:31]
	ds_read_b128 v[244:247], v96 offset:55392
	v_mfma_f32_32x32x16_bf16 v[0:15], v[212:215], v[252:255], v[0:15]
	ds_read_b128 v[212:215], v210 offset:18528
	ds_read_b128 v[252:255], v210 offset:23136
	s_waitcnt lgkmcnt(5)
	v_mfma_f32_32x32x16_bf16 v[32:47], v[216:219], v[224:227], v[32:47]
	s_waitcnt lgkmcnt(4)
	v_mfma_f32_32x32x16_bf16 v[48:63], v[216:219], v[220:223], v[48:63]
	ds_read_b128 v[216:219], v96 offset:60000
	s_waitcnt lgkmcnt(4)
	v_mfma_f32_32x32x16_bf16 v[16:31], v[228:231], v[224:227], v[16:31]
	v_mfma_f32_32x32x16_bf16 v[0:15], v[228:231], v[220:223], v[0:15]
	s_waitcnt lgkmcnt(2)
	v_mfma_f32_32x32x16_bf16 v[32:47], v[244:247], v[212:215], v[32:47]
	s_waitcnt lgkmcnt(1)
	v_mfma_f32_32x32x16_bf16 v[48:63], v[244:247], v[252:255], v[48:63]
	s_waitcnt lgkmcnt(0)
	v_mfma_f32_32x32x16_bf16 v[16:31], v[216:219], v[212:215], v[16:31]
	v_mfma_f32_32x32x16_bf16 v[0:15], v[216:219], v[252:255], v[0:15]
	s_setprio 0
	s_and_b64 vcc, exec, s[38:39]
	s_cbranch_vccnz .LBB0_325
	ds_write_b128 v209, v[64:67]
	ds_write_b128 v209, v[68:71] offset:4608
	ds_write_b128 v209, v[72:75] offset:9216
	ds_write_b128 v209, v[76:79] offset:13824
	ds_write_b128 v209, v[80:83] offset:36864
	ds_write_b128 v209, v[84:87] offset:41472
	ds_write_b128 v209, v[88:91] offset:46080
	ds_write_b128 v209, v[92:95] offset:50688
	v_add_co_u32_e32 v68, vcc, 0x2c000, v172
	global_load_dwordx4 v[64:67], v[172:173], off offset:256
	s_nop 0
	v_addc_co_u32_e32 v69, vcc, 0, v173, vcc
	v_add_co_u32_e32 v72, vcc, 0x58000, v172
	s_nop 1
	v_addc_co_u32_e32 v73, vcc, 0, v173, vcc
	v_add_co_u32_e32 v76, vcc, 0x84000, v172
	global_load_dwordx4 v[68:71], v[68:69], off offset:256
	s_nop 0
	global_load_dwordx4 v[72:75], v[72:73], off offset:256
	v_addc_co_u32_e32 v77, vcc, 0, v173, vcc
	v_add_co_u32_e32 v84, vcc, 0x2c000, v170
	global_load_dwordx4 v[76:79], v[76:77], off offset:256
	global_load_dwordx4 v[80:83], v[170:171], off offset:256
	v_addc_co_u32_e32 v85, vcc, 0, v171, vcc
	v_add_co_u32_e32 v88, vcc, 0x58000, v170
	s_nop 1
	v_addc_co_u32_e32 v89, vcc, 0, v171, vcc
	v_add_co_u32_e32 v92, vcc, 0x84000, v170
	global_load_dwordx4 v[84:87], v[84:85], off offset:256
	global_load_dwordx4 v[88:91], v[88:89], off offset:256
	v_addc_co_u32_e32 v93, vcc, 0, v171, vcc
	global_load_dwordx4 v[92:95], v[92:93], off offset:256
	s_branch .LBB0_325

.LBB0_338:
	s_ashr_i32 s3, s2, 1
	s_add_i32 s3, s3, s24
	s_ashr_i32 s4, s3, 31
	s_lshr_b32 s4, s4, 24
	s_add_i32 s4, s3, s4
	s_ashr_i32 s6, s4, 8
	s_lshl_b32 s6, s6, 5
	s_sub_i32 s7, 0x90, s6
	s_min_i32 s7, s7, 32
	s_abs_i32 s11, s7
	v_cvt_f32_u32_e32 v0, s11
	s_sub_i32 s12, 0, s11
	s_and_b32 s4, s4, 0xffffff00
	s_sub_i32 s3, s3, s4
	v_rcp_iflag_f32_e32 v0, v0
	s_abs_i32 s10, s3
	s_xor_b32 s4, s3, s7
	s_ashr_i32 s4, s4, 31
	v_mul_f32_e32 v0, 0x4f7ffffe, v0
	v_cvt_u32_f32_e32 v0, v0
	v_mov_b32_e32 v1, v162
	v_readfirstlane_b32 s13, v0
	s_mul_i32 s12, s12, s13
	s_mul_hi_u32 s12, s13, s12
	s_add_i32 s13, s13, s12
	s_mul_hi_u32 s12, s10, s13
	s_mul_i32 s13, s12, s11
	s_sub_i32 s10, s10, s13
	s_add_i32 s13, s12, 1
	s_sub_i32 s38, s10, s11
	s_cmp_ge_u32 s10, s11
	s_cselect_b32 s12, s13, s12
	s_cselect_b32 s10, s38, s10
	s_add_i32 s13, s12, 1
	s_cmp_ge_u32 s10, s11
	s_cselect_b32 s10, s13, s12
	s_xor_b32 s10, s10, s4
	s_sub_i32 s4, s10, s4
	s_mul_i32 s7, s4, s7
	s_sub_i32 s3, s3, s7
	s_add_i32 s3, s6, s3
	s_lshl_b32 s4, s4, 1
	s_and_b32 s6, s2, 1
	s_or_b32 s4, s4, s6
	s_mul_i32 s6, s3, 0xb0000
	s_mul_hi_i32 s7, s3, 0xb0000
	s_add_u32 s6, s56, s6
	s_addc_u32 s7, s57, s7
	v_lshlrev_b32_e32 v0, 3, v1
	v_ashrrev_i32_e32 v4, 3, v1
	v_and_b32_e32 v0, 56, v0
	v_mov_b64_e32 v[2:3], s[6:7]
	v_mad_i64_i32 v[2:3], s[6:7], v4, s18, v[2:3]
	v_lshlrev_b32_e32 v96, 1, v0
	v_lshl_add_u64 v[104:105], v[2:3], 0, v[96:97]
	v_add_co_u32_e32 v106, vcc, s19, v104
	s_mul_i32 s10, s4, 0x58000
	s_nop 0
	v_addc_co_u32_e32 v107, vcc, 0, v105, vcc
	s_waitcnt vmcnt(4)
	v_add_co_u32_e32 v92, vcc, s22, v104
	s_mul_hi_i32 s11, s4, 0x58000
	s_nop 0
	v_addc_co_u32_e32 v93, vcc, 0, v105, vcc
	v_add_co_u32_e32 v108, vcc, s20, v104
	s_add_u32 s10, s34, s10
	s_nop 0
	v_addc_co_u32_e32 v109, vcc, 0, v105, vcc
	s_addc_u32 s11, s27, s11
	v_add_co_u32_e32 v94, vcc, s23, v104
	v_mov_b64_e32 v[2:3], s[10:11]
	s_nop 0
	v_addc_co_u32_e32 v95, vcc, 0, v105, vcc
	v_mad_i64_i32 v[2:3], s[6:7], v4, s18, v[2:3]
	v_add_co_u32_e32 v110, vcc, s21, v104
	v_lshl_add_u64 v[102:103], v[2:3], 0, v[96:97]
	v_mad_u64_u32 v[24:25], s[6:7], v4, s84, v[0:1]
	v_and_b32_e32 v2, 31, v1
	v_lshrrev_b32_e32 v3, 1, v1
	v_lshrrev_b32_e32 v0, 2, v1
	v_addc_co_u32_e32 v111, vcc, 0, v105, vcc
	v_and_or_b32 v4, v3, s81, v2
	v_and_b32_e32 v0, 8, v0
	v_add_co_u32_e32 v98, vcc, s25, v104
	v_mad_u64_u32 v[26:27], s[6:7], v4, s84, v[0:1]
	v_and_or_b32 v1, v3, 32, v2
	v_addc_co_u32_e32 v99, vcc, 0, v105, vcc
	v_mad_u32_u24 v25, v1, s84, v0
	global_load_dwordx4 v[0:3], v[104:105], off
	global_load_dwordx4 v[4:7], v[92:93], off offset:-4096
	global_load_dwordx4 v[8:11], v[94:95], off offset:-4096
	global_load_dwordx4 v[12:15], v[98:99], off offset:-4096
	global_load_dwordx4 v[16:19], v[102:103], off
	v_add_co_u32_e32 v112, vcc, s19, v102
	v_lshl_add_u32 v96, v24, 1, 0
	s_nop 0
	v_addc_co_u32_e32 v113, vcc, 0, v103, vcc
	v_add_co_u32_e32 v100, vcc, s22, v102
	v_lshl_add_u32 v115, v26, 1, 0
	s_nop 0
	v_addc_co_u32_e32 v101, vcc, 0, v103, vcc
	global_load_dwordx4 v[20:23], v[100:101], off offset:-4096
	v_lshl_add_u32 v116, v25, 1, 0
	s_waitcnt vmcnt(5)
	ds_write_b128 v96, v[0:3]
	s_waitcnt vmcnt(4)
	ds_write_b128 v96, v[4:7] offset:4608
	s_waitcnt vmcnt(3)
	ds_write_b128 v96, v[8:11] offset:9216
	s_waitcnt vmcnt(2)
	ds_write_b128 v96, v[12:15] offset:13824
	s_waitcnt vmcnt(1)
	ds_write_b128 v96, v[16:19] offset:36864
	s_waitcnt vmcnt(0)
	ds_write_b128 v96, v[20:23] offset:41472
	global_load_dwordx4 v[56:59], v[104:105], off offset:128
	global_load_dwordx4 v[60:63], v[106:107], off offset:128
	global_load_dwordx4 v[64:67], v[108:109], off offset:128
	global_load_dwordx4 v[68:71], v[110:111], off offset:128
	global_load_dwordx4 v[72:75], v[102:103], off offset:128
	global_load_dwordx4 v[76:79], v[112:113], off offset:128
	global_load_dwordx4 v[32:35], v[104:105], off offset:256
	global_load_dwordx4 v[36:39], v[106:107], off offset:256
	global_load_dwordx4 v[40:43], v[108:109], off offset:256
	global_load_dwordx4 v[44:47], v[110:111], off offset:256
	global_load_dwordx4 v[48:51], v[102:103], off offset:256
	global_load_dwordx4 v[52:55], v[112:113], off offset:256
	s_waitcnt lgkmcnt(0)
	s_barrier
	s_setprio 1
	ds_read_b128 v[212:215], v116 offset:36864
	ds_read_b128 v[216:219], v115
	ds_read_b128 v[220:223], v115 offset:4608
	ds_read_b128 v[224:227], v116 offset:36896
	ds_read_b128 v[228:231], v115 offset:32
	ds_read_b128 v[244:247], v115 offset:4640
	ds_read_b128 v[252:255], v116 offset:36928
	s_waitcnt lgkmcnt(5)
	v_mfma_f32_32x32x16_bf16 v[0:15], v[212:215], v[216:219], 0
	ds_read_b128 v[216:219], v115 offset:64
	s_waitcnt lgkmcnt(5)
	v_mfma_f32_32x32x16_bf16 v[16:31], v[212:215], v[220:223], 0
	ds_read_b128 v[212:215], v115 offset:4672
	ds_read_b128 v[220:223], v116 offset:36960
	s_waitcnt lgkmcnt(5)
	v_mfma_f32_32x32x16_bf16 v[0:15], v[224:227], v[228:231], v[0:15]
	ds_read_b128 v[228:231], v115 offset:96
	s_waitcnt lgkmcnt(5)
	v_mfma_f32_32x32x16_bf16 v[16:31], v[224:227], v[244:247], v[16:31]
	ds_read_b128 v[224:227], v115 offset:4704
	s_waitcnt lgkmcnt(4)
	v_mfma_f32_32x32x16_bf16 v[0:15], v[252:255], v[216:219], v[0:15]
	s_waitcnt lgkmcnt(3)
	v_mfma_f32_32x32x16_bf16 v[16:31], v[252:255], v[212:215], v[16:31]
	s_waitcnt lgkmcnt(1)
	v_mfma_f32_32x32x16_bf16 v[0:15], v[220:223], v[228:231], v[0:15]
	s_waitcnt lgkmcnt(0)
	v_mfma_f32_32x32x16_bf16 v[16:31], v[220:223], v[224:227], v[16:31]
	s_waitcnt vmcnt(11)
	ds_write_b128 v96, v[56:59] offset:18432
	global_load_dwordx4 v[56:59], v[104:105], off offset:384
	s_waitcnt vmcnt(11)
	ds_write_b128 v96, v[60:63] offset:23040
	global_load_dwordx4 v[60:63], v[106:107], off offset:384
	s_waitcnt vmcnt(11)
	ds_write_b128 v96, v[64:67] offset:27648
	global_load_dwordx4 v[64:67], v[108:109], off offset:384
	s_waitcnt vmcnt(11)
	ds_write_b128 v96, v[68:71] offset:32256
	global_load_dwordx4 v[68:71], v[110:111], off offset:384
	s_waitcnt vmcnt(11)
	ds_write_b128 v96, v[72:75] offset:55296
	global_load_dwordx4 v[72:75], v[102:103], off offset:384
	s_waitcnt vmcnt(11)
	ds_write_b128 v96, v[76:79] offset:59904
	global_load_dwordx4 v[80:83], v[112:113], off offset:384
	s_setprio 0
	s_waitcnt lgkmcnt(0)
	s_barrier
	s_setprio 1
	ds_read_b128 v[212:215], v116 offset:55296
	ds_read_b128 v[216:219], v115 offset:18432
	ds_read_b128 v[220:223], v115 offset:23040
	ds_read_b128 v[224:227], v116 offset:55328
	ds_read_b128 v[228:231], v115 offset:18464
	ds_read_b128 v[244:247], v115 offset:23072
	ds_read_b128 v[252:255], v116 offset:55360
	s_waitcnt lgkmcnt(5)
	v_mfma_f32_32x32x16_bf16 v[0:15], v[212:215], v[216:219], v[0:15]
	ds_read_b128 v[216:219], v115 offset:18496
	s_waitcnt lgkmcnt(5)
	v_mfma_f32_32x32x16_bf16 v[16:31], v[212:215], v[220:223], v[16:31]
	ds_read_b128 v[212:215], v115 offset:23104
	ds_read_b128 v[220:223], v116 offset:55392
	s_waitcnt lgkmcnt(5)
	v_mfma_f32_32x32x16_bf16 v[0:15], v[224:227], v[228:231], v[0:15]
	ds_read_b128 v[228:231], v115 offset:18528
	s_waitcnt lgkmcnt(5)
	v_mfma_f32_32x32x16_bf16 v[16:31], v[224:227], v[244:247], v[16:31]
	ds_read_b128 v[224:227], v115 offset:23136
	s_waitcnt lgkmcnt(4)
	v_mfma_f32_32x32x16_bf16 v[0:15], v[252:255], v[216:219], v[0:15]
	s_waitcnt lgkmcnt(3)
	v_mfma_f32_32x32x16_bf16 v[16:31], v[252:255], v[212:215], v[16:31]
	s_waitcnt lgkmcnt(1)
	v_mfma_f32_32x32x16_bf16 v[0:15], v[220:223], v[228:231], v[0:15]
	s_waitcnt lgkmcnt(0)
	v_mfma_f32_32x32x16_bf16 v[16:31], v[220:223], v[224:227], v[16:31]
	s_waitcnt vmcnt(11)
	ds_write_b128 v96, v[32:35]
	global_load_dwordx4 v[32:35], v[104:105], off offset:512
	s_waitcnt vmcnt(11)
	ds_write_b128 v96, v[36:39] offset:4608
	s_waitcnt vmcnt(10)
	ds_write_b128 v96, v[40:43] offset:9216
	global_load_dwordx4 v[40:43], v[106:107], off offset:512
	s_waitcnt vmcnt(10)
	ds_write_b128 v96, v[44:47] offset:13824
	global_load_dwordx4 v[44:47], v[108:109], off offset:512
	s_waitcnt vmcnt(10)
	ds_write_b128 v96, v[48:51] offset:36864
	global_load_dwordx4 v[48:51], v[110:111], off offset:512
	global_load_dwordx4 v[76:79], v[102:103], off offset:512
	s_waitcnt vmcnt(11)
	ds_write_b128 v96, v[52:55] offset:41472
	global_load_dwordx4 v[84:87], v[112:113], off offset:512
	s_setprio 0
	s_waitcnt lgkmcnt(0)
	s_barrier
	s_setprio 1
	ds_read_b128 v[212:215], v116 offset:36864
	ds_read_b128 v[216:219], v115
	ds_read_b128 v[220:223], v115 offset:4608
	ds_read_b128 v[224:227], v116 offset:36896
	ds_read_b128 v[228:231], v115 offset:32
	ds_read_b128 v[244:247], v115 offset:4640
	ds_read_b128 v[252:255], v116 offset:36928
	s_waitcnt lgkmcnt(5)
	v_mfma_f32_32x32x16_bf16 v[0:15], v[212:215], v[216:219], v[0:15]
	ds_read_b128 v[216:219], v115 offset:64
	s_waitcnt lgkmcnt(5)
	v_mfma_f32_32x32x16_bf16 v[16:31], v[212:215], v[220:223], v[16:31]
	ds_read_b128 v[212:215], v115 offset:4672
	ds_read_b128 v[220:223], v116 offset:36960
	s_waitcnt lgkmcnt(5)
	v_mfma_f32_32x32x16_bf16 v[0:15], v[224:227], v[228:231], v[0:15]
	ds_read_b128 v[228:231], v115 offset:96
	s_waitcnt lgkmcnt(5)
	v_mfma_f32_32x32x16_bf16 v[16:31], v[224:227], v[244:247], v[16:31]
	ds_read_b128 v[224:227], v115 offset:4704
	s_waitcnt lgkmcnt(4)
	v_mfma_f32_32x32x16_bf16 v[0:15], v[252:255], v[216:219], v[0:15]
	s_waitcnt lgkmcnt(3)
	v_mfma_f32_32x32x16_bf16 v[16:31], v[252:255], v[212:215], v[16:31]
	s_waitcnt lgkmcnt(1)
	v_mfma_f32_32x32x16_bf16 v[0:15], v[220:223], v[228:231], v[0:15]
	s_waitcnt lgkmcnt(0)
	v_mfma_f32_32x32x16_bf16 v[16:31], v[220:223], v[224:227], v[16:31]
	s_waitcnt vmcnt(11)
	ds_write_b128 v96, v[56:59] offset:18432
	global_load_dwordx4 v[36:39], v[104:105], off offset:640
	s_waitcnt vmcnt(11)
	ds_write_b128 v96, v[60:63] offset:23040
	global_load_dwordx4 v[52:55], v[106:107], off offset:640
	s_waitcnt vmcnt(11)
	ds_write_b128 v96, v[64:67] offset:27648
	global_load_dwordx4 v[56:59], v[108:109], off offset:640
	s_waitcnt vmcnt(11)
	ds_write_b128 v96, v[68:71] offset:32256
	global_load_dwordx4 v[60:63], v[110:111], off offset:640
	s_waitcnt vmcnt(11)
	ds_write_b128 v96, v[72:75] offset:55296
	global_load_dwordx4 v[64:67], v[102:103], off offset:640
	s_waitcnt vmcnt(11)
	ds_write_b128 v96, v[80:83] offset:59904
	global_load_dwordx4 v[72:75], v[112:113], off offset:640
	s_setprio 0
	s_waitcnt lgkmcnt(0)
	s_barrier
	s_setprio 1
	ds_read_b128 v[212:215], v116 offset:55296
	ds_read_b128 v[216:219], v115 offset:18432
	ds_read_b128 v[220:223], v115 offset:23040
	ds_read_b128 v[224:227], v116 offset:55328
	ds_read_b128 v[228:231], v115 offset:18464
	ds_read_b128 v[244:247], v115 offset:23072
	ds_read_b128 v[252:255], v116 offset:55360
	s_waitcnt lgkmcnt(5)
	v_mfma_f32_32x32x16_bf16 v[0:15], v[212:215], v[216:219], v[0:15]
	ds_read_b128 v[216:219], v115 offset:18496
	s_waitcnt lgkmcnt(5)
	v_mfma_f32_32x32x16_bf16 v[16:31], v[212:215], v[220:223], v[16:31]
	ds_read_b128 v[212:215], v115 offset:23104
	ds_read_b128 v[220:223], v116 offset:55392
	s_waitcnt lgkmcnt(5)
	v_mfma_f32_32x32x16_bf16 v[0:15], v[224:227], v[228:231], v[0:15]
	ds_read_b128 v[228:231], v115 offset:18528
	s_waitcnt lgkmcnt(5)
	v_mfma_f32_32x32x16_bf16 v[16:31], v[224:227], v[244:247], v[16:31]
	ds_read_b128 v[224:227], v115 offset:23136
	s_waitcnt lgkmcnt(4)
	v_mfma_f32_32x32x16_bf16 v[0:15], v[252:255], v[216:219], v[0:15]
	s_waitcnt lgkmcnt(3)
	v_mfma_f32_32x32x16_bf16 v[16:31], v[252:255], v[212:215], v[16:31]
	s_waitcnt lgkmcnt(1)
	v_mfma_f32_32x32x16_bf16 v[0:15], v[220:223], v[228:231], v[0:15]
	s_waitcnt lgkmcnt(0)
	v_mfma_f32_32x32x16_bf16 v[16:31], v[220:223], v[224:227], v[16:31]
	s_waitcnt vmcnt(11)
	ds_write_b128 v96, v[32:35]
	global_load_dwordx4 v[32:35], v[104:105], off offset:768
	s_waitcnt vmcnt(11)
	ds_write_b128 v96, v[40:43] offset:4608
	global_load_dwordx4 v[40:43], v[106:107], off offset:768
	s_waitcnt vmcnt(11)
	ds_write_b128 v96, v[44:47] offset:9216
	global_load_dwordx4 v[44:47], v[108:109], off offset:768
	s_waitcnt vmcnt(11)
	ds_write_b128 v96, v[48:51] offset:13824
	global_load_dwordx4 v[48:51], v[110:111], off offset:768
	s_waitcnt vmcnt(11)
	ds_write_b128 v96, v[76:79] offset:36864
	global_load_dwordx4 v[68:71], v[102:103], off offset:768
	s_waitcnt vmcnt(11)
	ds_write_b128 v96, v[84:87] offset:41472
	global_load_dwordx4 v[76:79], v[112:113], off offset:768
	s_setprio 0
	s_waitcnt lgkmcnt(0)
	s_barrier
	s_setprio 1
	ds_read_b128 v[212:215], v116 offset:36864
	ds_read_b128 v[216:219], v115
	ds_read_b128 v[220:223], v115 offset:4608
	ds_read_b128 v[224:227], v116 offset:36896
	ds_read_b128 v[228:231], v115 offset:32
	ds_read_b128 v[244:247], v115 offset:4640
	ds_read_b128 v[252:255], v116 offset:36928
	s_waitcnt lgkmcnt(5)
	v_mfma_f32_32x32x16_bf16 v[0:15], v[212:215], v[216:219], v[0:15]
	ds_read_b128 v[216:219], v115 offset:64
	s_waitcnt lgkmcnt(5)
	v_mfma_f32_32x32x16_bf16 v[16:31], v[212:215], v[220:223], v[16:31]
	ds_read_b128 v[212:215], v115 offset:4672
	ds_read_b128 v[220:223], v116 offset:36960
	s_waitcnt lgkmcnt(5)
	v_mfma_f32_32x32x16_bf16 v[0:15], v[224:227], v[228:231], v[0:15]
	ds_read_b128 v[228:231], v115 offset:96
	s_waitcnt lgkmcnt(5)
	v_mfma_f32_32x32x16_bf16 v[16:31], v[224:227], v[244:247], v[16:31]
	ds_read_b128 v[224:227], v115 offset:4704
	s_waitcnt lgkmcnt(4)
	v_mfma_f32_32x32x16_bf16 v[0:15], v[252:255], v[216:219], v[0:15]
	s_waitcnt lgkmcnt(3)
	v_mfma_f32_32x32x16_bf16 v[16:31], v[252:255], v[212:215], v[16:31]
	s_waitcnt lgkmcnt(1)
	v_mfma_f32_32x32x16_bf16 v[0:15], v[220:223], v[228:231], v[0:15]
	s_waitcnt lgkmcnt(0)
	v_mfma_f32_32x32x16_bf16 v[16:31], v[220:223], v[224:227], v[16:31]
	s_waitcnt vmcnt(11)
	ds_write_b128 v96, v[36:39] offset:18432
	global_load_dwordx4 v[36:39], v[104:105], off offset:896
	s_waitcnt vmcnt(11)
	ds_write_b128 v96, v[52:55] offset:23040
	global_load_dwordx4 v[52:55], v[106:107], off offset:896
	s_waitcnt vmcnt(11)
	ds_write_b128 v96, v[56:59] offset:27648
	global_load_dwordx4 v[56:59], v[108:109], off offset:896
	s_waitcnt vmcnt(11)
	ds_write_b128 v96, v[60:63] offset:32256
	global_load_dwordx4 v[60:63], v[110:111], off offset:896
	s_waitcnt vmcnt(11)
	ds_write_b128 v96, v[64:67] offset:55296
	global_load_dwordx4 v[64:67], v[102:103], off offset:896
	s_waitcnt vmcnt(11)
	ds_write_b128 v96, v[72:75] offset:59904
	global_load_dwordx4 v[72:75], v[112:113], off offset:896
	s_setprio 0
	s_waitcnt lgkmcnt(0)
	s_barrier
	s_setprio 1
	ds_read_b128 v[212:215], v116 offset:55296
	ds_read_b128 v[216:219], v115 offset:18432
	ds_read_b128 v[220:223], v115 offset:23040
	ds_read_b128 v[224:227], v116 offset:55328
	ds_read_b128 v[228:231], v115 offset:18464
	ds_read_b128 v[244:247], v115 offset:23072
	ds_read_b128 v[252:255], v116 offset:55360
	s_waitcnt lgkmcnt(5)
	v_mfma_f32_32x32x16_bf16 v[0:15], v[212:215], v[216:219], v[0:15]
	ds_read_b128 v[216:219], v115 offset:18496
	s_waitcnt lgkmcnt(5)
	v_mfma_f32_32x32x16_bf16 v[16:31], v[212:215], v[220:223], v[16:31]
	ds_read_b128 v[212:215], v115 offset:23104
	ds_read_b128 v[220:223], v116 offset:55392
	s_waitcnt lgkmcnt(5)
	v_mfma_f32_32x32x16_bf16 v[0:15], v[224:227], v[228:231], v[0:15]
	ds_read_b128 v[228:231], v115 offset:18528
	s_waitcnt lgkmcnt(5)
	v_mfma_f32_32x32x16_bf16 v[16:31], v[224:227], v[244:247], v[16:31]
	ds_read_b128 v[224:227], v115 offset:23136
	s_waitcnt lgkmcnt(4)
	v_mfma_f32_32x32x16_bf16 v[0:15], v[252:255], v[216:219], v[0:15]
	s_waitcnt lgkmcnt(3)
	v_mfma_f32_32x32x16_bf16 v[16:31], v[252:255], v[212:215], v[16:31]
	s_waitcnt lgkmcnt(1)
	v_mfma_f32_32x32x16_bf16 v[0:15], v[220:223], v[228:231], v[0:15]
	s_waitcnt lgkmcnt(0)
	v_mfma_f32_32x32x16_bf16 v[16:31], v[220:223], v[224:227], v[16:31]
	s_waitcnt vmcnt(11)
	ds_write_b128 v96, v[32:35]
	global_load_dwordx4 v[32:35], v[104:105], off offset:1024
	s_waitcnt vmcnt(11)
	ds_write_b128 v96, v[40:43] offset:4608
	global_load_dwordx4 v[40:43], v[106:107], off offset:1024
	s_waitcnt vmcnt(11)
	ds_write_b128 v96, v[44:47] offset:9216
	global_load_dwordx4 v[44:47], v[108:109], off offset:1024
	s_waitcnt vmcnt(11)
	ds_write_b128 v96, v[48:51] offset:13824
	global_load_dwordx4 v[48:51], v[110:111], off offset:1024
	s_waitcnt vmcnt(11)
	ds_write_b128 v96, v[68:71] offset:36864
	global_load_dwordx4 v[68:71], v[102:103], off offset:1024
	s_waitcnt vmcnt(11)
	ds_write_b128 v96, v[76:79] offset:41472
	global_load_dwordx4 v[76:79], v[112:113], off offset:1024
	s_setprio 0
	s_waitcnt lgkmcnt(0)
	s_barrier
	s_setprio 1
	ds_read_b128 v[212:215], v116 offset:36864
	ds_read_b128 v[216:219], v115
	ds_read_b128 v[220:223], v115 offset:4608
	ds_read_b128 v[224:227], v116 offset:36896
	ds_read_b128 v[228:231], v115 offset:32
	ds_read_b128 v[244:247], v115 offset:4640
	ds_read_b128 v[252:255], v116 offset:36928
	s_waitcnt lgkmcnt(5)
	v_mfma_f32_32x32x16_bf16 v[0:15], v[212:215], v[216:219], v[0:15]
	ds_read_b128 v[216:219], v115 offset:64
	s_waitcnt lgkmcnt(5)
	v_mfma_f32_32x32x16_bf16 v[16:31], v[212:215], v[220:223], v[16:31]
	ds_read_b128 v[212:215], v115 offset:4672
	ds_read_b128 v[220:223], v116 offset:36960
	s_waitcnt lgkmcnt(5)
	v_mfma_f32_32x32x16_bf16 v[0:15], v[224:227], v[228:231], v[0:15]
	ds_read_b128 v[228:231], v115 offset:96
	s_waitcnt lgkmcnt(5)
	v_mfma_f32_32x32x16_bf16 v[16:31], v[224:227], v[244:247], v[16:31]
	ds_read_b128 v[224:227], v115 offset:4704
	s_waitcnt lgkmcnt(4)
	v_mfma_f32_32x32x16_bf16 v[0:15], v[252:255], v[216:219], v[0:15]
	s_waitcnt lgkmcnt(3)
	v_mfma_f32_32x32x16_bf16 v[16:31], v[252:255], v[212:215], v[16:31]
	s_waitcnt lgkmcnt(1)
	v_mfma_f32_32x32x16_bf16 v[0:15], v[220:223], v[228:231], v[0:15]
	s_waitcnt lgkmcnt(0)
	v_mfma_f32_32x32x16_bf16 v[16:31], v[220:223], v[224:227], v[16:31]
	s_waitcnt vmcnt(11)
	ds_write_b128 v96, v[36:39] offset:18432
	global_load_dwordx4 v[36:39], v[104:105], off offset:1152
	s_waitcnt vmcnt(11)
	ds_write_b128 v96, v[52:55] offset:23040
	global_load_dwordx4 v[52:55], v[106:107], off offset:1152
	s_waitcnt vmcnt(11)
	ds_write_b128 v96, v[56:59] offset:27648
	global_load_dwordx4 v[56:59], v[108:109], off offset:1152
	s_waitcnt vmcnt(11)
	ds_write_b128 v96, v[60:63] offset:32256
	global_load_dwordx4 v[60:63], v[110:111], off offset:1152
	s_waitcnt vmcnt(11)
	ds_write_b128 v96, v[64:67] offset:55296
	global_load_dwordx4 v[64:67], v[102:103], off offset:1152
	s_waitcnt vmcnt(11)
	ds_write_b128 v96, v[72:75] offset:59904
	global_load_dwordx4 v[72:75], v[112:113], off offset:1152
	s_setprio 0
	s_waitcnt lgkmcnt(0)
	s_barrier
	s_setprio 1
	ds_read_b128 v[212:215], v116 offset:55296
	ds_read_b128 v[216:219], v115 offset:18432
	ds_read_b128 v[220:223], v115 offset:23040
	ds_read_b128 v[224:227], v116 offset:55328
	ds_read_b128 v[228:231], v115 offset:18464
	ds_read_b128 v[244:247], v115 offset:23072
	ds_read_b128 v[252:255], v116 offset:55360
	s_waitcnt lgkmcnt(5)
	v_mfma_f32_32x32x16_bf16 v[0:15], v[212:215], v[216:219], v[0:15]
	ds_read_b128 v[216:219], v115 offset:18496
	s_waitcnt lgkmcnt(5)
	v_mfma_f32_32x32x16_bf16 v[16:31], v[212:215], v[220:223], v[16:31]
	ds_read_b128 v[212:215], v115 offset:23104
	ds_read_b128 v[220:223], v116 offset:55392
	s_waitcnt lgkmcnt(5)
	v_mfma_f32_32x32x16_bf16 v[0:15], v[224:227], v[228:231], v[0:15]
	ds_read_b128 v[228:231], v115 offset:18528
	s_waitcnt lgkmcnt(5)
	v_mfma_f32_32x32x16_bf16 v[16:31], v[224:227], v[244:247], v[16:31]
	ds_read_b128 v[224:227], v115 offset:23136
	s_waitcnt lgkmcnt(4)
	v_mfma_f32_32x32x16_bf16 v[0:15], v[252:255], v[216:219], v[0:15]
	s_waitcnt lgkmcnt(3)
	v_mfma_f32_32x32x16_bf16 v[16:31], v[252:255], v[212:215], v[16:31]
	s_waitcnt lgkmcnt(1)
	v_mfma_f32_32x32x16_bf16 v[0:15], v[220:223], v[228:231], v[0:15]
	s_waitcnt lgkmcnt(0)
	v_mfma_f32_32x32x16_bf16 v[16:31], v[220:223], v[224:227], v[16:31]
	s_waitcnt vmcnt(11)
	ds_write_b128 v96, v[32:35]
	global_load_dwordx4 v[32:35], v[104:105], off offset:1280
	s_waitcnt vmcnt(11)
	ds_write_b128 v96, v[40:43] offset:4608
	global_load_dwordx4 v[40:43], v[106:107], off offset:1280
	s_waitcnt vmcnt(11)
	ds_write_b128 v96, v[44:47] offset:9216
	global_load_dwordx4 v[44:47], v[108:109], off offset:1280
	s_waitcnt vmcnt(11)
	ds_write_b128 v96, v[48:51] offset:13824
	global_load_dwordx4 v[48:51], v[110:111], off offset:1280
	s_waitcnt vmcnt(11)
	ds_write_b128 v96, v[68:71] offset:36864
	global_load_dwordx4 v[68:71], v[102:103], off offset:1280
	s_waitcnt vmcnt(11)
	ds_write_b128 v96, v[76:79] offset:41472
	global_load_dwordx4 v[76:79], v[112:113], off offset:1280
	s_setprio 0
	s_waitcnt lgkmcnt(0)
	s_barrier
	s_setprio 1
	ds_read_b128 v[212:215], v116 offset:36864
	ds_read_b128 v[216:219], v115
	ds_read_b128 v[220:223], v115 offset:4608
	ds_read_b128 v[224:227], v116 offset:36896
	ds_read_b128 v[228:231], v115 offset:32
	ds_read_b128 v[244:247], v115 offset:4640
	ds_read_b128 v[252:255], v116 offset:36928
	s_waitcnt lgkmcnt(5)
	v_mfma_f32_32x32x16_bf16 v[0:15], v[212:215], v[216:219], v[0:15]
	ds_read_b128 v[216:219], v115 offset:64
	s_waitcnt lgkmcnt(5)
	v_mfma_f32_32x32x16_bf16 v[16:31], v[212:215], v[220:223], v[16:31]
	ds_read_b128 v[212:215], v115 offset:4672
	ds_read_b128 v[220:223], v116 offset:36960
	s_waitcnt lgkmcnt(5)
	v_mfma_f32_32x32x16_bf16 v[0:15], v[224:227], v[228:231], v[0:15]
	ds_read_b128 v[228:231], v115 offset:96
	s_waitcnt lgkmcnt(5)
	v_mfma_f32_32x32x16_bf16 v[16:31], v[224:227], v[244:247], v[16:31]
	ds_read_b128 v[224:227], v115 offset:4704
	s_waitcnt lgkmcnt(4)
	v_mfma_f32_32x32x16_bf16 v[0:15], v[252:255], v[216:219], v[0:15]
	s_waitcnt lgkmcnt(3)
	v_mfma_f32_32x32x16_bf16 v[16:31], v[252:255], v[212:215], v[16:31]
	s_waitcnt lgkmcnt(1)
	v_mfma_f32_32x32x16_bf16 v[0:15], v[220:223], v[228:231], v[0:15]
	s_waitcnt lgkmcnt(0)
	v_mfma_f32_32x32x16_bf16 v[16:31], v[220:223], v[224:227], v[16:31]
	s_waitcnt vmcnt(11)
	ds_write_b128 v96, v[36:39] offset:18432
	global_load_dwordx4 v[36:39], v[104:105], off offset:1408
	s_waitcnt vmcnt(11)
	ds_write_b128 v96, v[52:55] offset:23040
	global_load_dwordx4 v[52:55], v[106:107], off offset:1408
	s_waitcnt vmcnt(11)
	ds_write_b128 v96, v[56:59] offset:27648
	global_load_dwordx4 v[56:59], v[108:109], off offset:1408
	s_waitcnt vmcnt(11)
	ds_write_b128 v96, v[60:63] offset:32256
	global_load_dwordx4 v[60:63], v[110:111], off offset:1408
	s_waitcnt vmcnt(11)
	ds_write_b128 v96, v[64:67] offset:55296
	global_load_dwordx4 v[64:67], v[102:103], off offset:1408
	s_waitcnt vmcnt(11)
	ds_write_b128 v96, v[72:75] offset:59904
	global_load_dwordx4 v[72:75], v[112:113], off offset:1408
	s_setprio 0
	s_waitcnt lgkmcnt(0)
	s_barrier
	s_setprio 1
	ds_read_b128 v[212:215], v116 offset:55296
	ds_read_b128 v[216:219], v115 offset:18432
	ds_read_b128 v[220:223], v115 offset:23040
	ds_read_b128 v[224:227], v116 offset:55328
	ds_read_b128 v[228:231], v115 offset:18464
	ds_read_b128 v[244:247], v115 offset:23072
	ds_read_b128 v[252:255], v116 offset:55360
	s_waitcnt lgkmcnt(5)
	v_mfma_f32_32x32x16_bf16 v[0:15], v[212:215], v[216:219], v[0:15]
	ds_read_b128 v[216:219], v115 offset:18496
	s_waitcnt lgkmcnt(5)
	v_mfma_f32_32x32x16_bf16 v[16:31], v[212:215], v[220:223], v[16:31]
	ds_read_b128 v[212:215], v115 offset:23104
	ds_read_b128 v[220:223], v116 offset:55392
	s_waitcnt lgkmcnt(5)
	v_mfma_f32_32x32x16_bf16 v[0:15], v[224:227], v[228:231], v[0:15]
	ds_read_b128 v[228:231], v115 offset:18528
	s_waitcnt lgkmcnt(5)
	v_mfma_f32_32x32x16_bf16 v[16:31], v[224:227], v[244:247], v[16:31]
	ds_read_b128 v[224:227], v115 offset:23136
	s_waitcnt lgkmcnt(4)
	v_mfma_f32_32x32x16_bf16 v[0:15], v[252:255], v[216:219], v[0:15]
	s_waitcnt lgkmcnt(3)
	v_mfma_f32_32x32x16_bf16 v[16:31], v[252:255], v[212:215], v[16:31]
	s_waitcnt lgkmcnt(1)
	v_mfma_f32_32x32x16_bf16 v[0:15], v[220:223], v[228:231], v[0:15]
	s_waitcnt lgkmcnt(0)
	v_mfma_f32_32x32x16_bf16 v[16:31], v[220:223], v[224:227], v[16:31]
	s_waitcnt vmcnt(11)
	ds_write_b128 v96, v[32:35]
	global_load_dwordx4 v[32:35], v[104:105], off offset:1536
	s_waitcnt vmcnt(11)
	ds_write_b128 v96, v[40:43] offset:4608
	global_load_dwordx4 v[40:43], v[106:107], off offset:1536
	s_waitcnt vmcnt(11)
	ds_write_b128 v96, v[44:47] offset:9216
	global_load_dwordx4 v[44:47], v[108:109], off offset:1536
	s_waitcnt vmcnt(11)
	ds_write_b128 v96, v[48:51] offset:13824
	global_load_dwordx4 v[48:51], v[110:111], off offset:1536
	s_waitcnt vmcnt(11)
	ds_write_b128 v96, v[68:71] offset:36864
	global_load_dwordx4 v[68:71], v[102:103], off offset:1536
	s_waitcnt vmcnt(11)
	ds_write_b128 v96, v[76:79] offset:41472
	global_load_dwordx4 v[76:79], v[112:113], off offset:1536
	s_setprio 0
	s_waitcnt lgkmcnt(0)
	s_barrier
	s_setprio 1
	ds_read_b128 v[212:215], v116 offset:36864
	ds_read_b128 v[216:219], v115
	ds_read_b128 v[220:223], v115 offset:4608
	ds_read_b128 v[224:227], v116 offset:36896
	ds_read_b128 v[228:231], v115 offset:32
	ds_read_b128 v[244:247], v115 offset:4640
	ds_read_b128 v[252:255], v116 offset:36928
	s_waitcnt lgkmcnt(5)
	v_mfma_f32_32x32x16_bf16 v[0:15], v[212:215], v[216:219], v[0:15]
	ds_read_b128 v[216:219], v115 offset:64
	s_waitcnt lgkmcnt(5)
	v_mfma_f32_32x32x16_bf16 v[16:31], v[212:215], v[220:223], v[16:31]
	ds_read_b128 v[212:215], v115 offset:4672
	ds_read_b128 v[220:223], v116 offset:36960
	s_waitcnt lgkmcnt(5)
	v_mfma_f32_32x32x16_bf16 v[0:15], v[224:227], v[228:231], v[0:15]
	ds_read_b128 v[228:231], v115 offset:96
	s_waitcnt lgkmcnt(5)
	v_mfma_f32_32x32x16_bf16 v[16:31], v[224:227], v[244:247], v[16:31]
	ds_read_b128 v[224:227], v115 offset:4704
	s_waitcnt lgkmcnt(4)
	v_mfma_f32_32x32x16_bf16 v[0:15], v[252:255], v[216:219], v[0:15]
	s_waitcnt lgkmcnt(3)
	v_mfma_f32_32x32x16_bf16 v[16:31], v[252:255], v[212:215], v[16:31]
	s_waitcnt lgkmcnt(1)
	v_mfma_f32_32x32x16_bf16 v[0:15], v[220:223], v[228:231], v[0:15]
	s_waitcnt lgkmcnt(0)
	v_mfma_f32_32x32x16_bf16 v[16:31], v[220:223], v[224:227], v[16:31]
	s_waitcnt vmcnt(11)
	ds_write_b128 v96, v[36:39] offset:18432
	global_load_dwordx4 v[36:39], v[104:105], off offset:1664
	s_waitcnt vmcnt(11)
	ds_write_b128 v96, v[52:55] offset:23040
	global_load_dwordx4 v[52:55], v[106:107], off offset:1664
	s_waitcnt vmcnt(11)
	ds_write_b128 v96, v[56:59] offset:27648
	global_load_dwordx4 v[56:59], v[108:109], off offset:1664
	s_waitcnt vmcnt(11)
	ds_write_b128 v96, v[60:63] offset:32256
	global_load_dwordx4 v[60:63], v[110:111], off offset:1664
	s_waitcnt vmcnt(11)
	ds_write_b128 v96, v[64:67] offset:55296
	global_load_dwordx4 v[64:67], v[102:103], off offset:1664
	s_waitcnt vmcnt(11)
	ds_write_b128 v96, v[72:75] offset:59904
	global_load_dwordx4 v[72:75], v[112:113], off offset:1664
	s_setprio 0
	s_waitcnt lgkmcnt(0)
	s_barrier
	s_setprio 1
	ds_read_b128 v[212:215], v116 offset:55296
	ds_read_b128 v[216:219], v115 offset:18432
	ds_read_b128 v[220:223], v115 offset:23040
	ds_read_b128 v[224:227], v116 offset:55328
	ds_read_b128 v[228:231], v115 offset:18464
	ds_read_b128 v[244:247], v115 offset:23072
	ds_read_b128 v[252:255], v116 offset:55360
	s_waitcnt lgkmcnt(5)
	v_mfma_f32_32x32x16_bf16 v[0:15], v[212:215], v[216:219], v[0:15]
	ds_read_b128 v[216:219], v115 offset:18496
	s_waitcnt lgkmcnt(5)
	v_mfma_f32_32x32x16_bf16 v[16:31], v[212:215], v[220:223], v[16:31]
	ds_read_b128 v[212:215], v115 offset:23104
	ds_read_b128 v[220:223], v116 offset:55392
	s_waitcnt lgkmcnt(5)
	v_mfma_f32_32x32x16_bf16 v[0:15], v[224:227], v[228:231], v[0:15]
	ds_read_b128 v[228:231], v115 offset:18528
	s_waitcnt lgkmcnt(5)
	v_mfma_f32_32x32x16_bf16 v[16:31], v[224:227], v[244:247], v[16:31]
	ds_read_b128 v[224:227], v115 offset:23136
	s_waitcnt lgkmcnt(4)
	v_mfma_f32_32x32x16_bf16 v[0:15], v[252:255], v[216:219], v[0:15]
	s_waitcnt lgkmcnt(3)
	v_mfma_f32_32x32x16_bf16 v[16:31], v[252:255], v[212:215], v[16:31]
	s_waitcnt lgkmcnt(1)
	v_mfma_f32_32x32x16_bf16 v[0:15], v[220:223], v[228:231], v[0:15]
	s_waitcnt lgkmcnt(0)
	v_mfma_f32_32x32x16_bf16 v[16:31], v[220:223], v[224:227], v[16:31]
	s_waitcnt vmcnt(11)
	ds_write_b128 v96, v[32:35]
	global_load_dwordx4 v[32:35], v[104:105], off offset:1792
	s_waitcnt vmcnt(11)
	ds_write_b128 v96, v[40:43] offset:4608
	global_load_dwordx4 v[40:43], v[106:107], off offset:1792
	s_waitcnt vmcnt(11)
	ds_write_b128 v96, v[44:47] offset:9216
	global_load_dwordx4 v[44:47], v[108:109], off offset:1792
	s_waitcnt vmcnt(11)
	ds_write_b128 v96, v[48:51] offset:13824
	global_load_dwordx4 v[48:51], v[110:111], off offset:1792
	s_waitcnt vmcnt(11)
	ds_write_b128 v96, v[68:71] offset:36864
	global_load_dwordx4 v[68:71], v[102:103], off offset:1792
	s_waitcnt vmcnt(11)
	ds_write_b128 v96, v[76:79] offset:41472
	global_load_dwordx4 v[76:79], v[112:113], off offset:1792
	s_setprio 0
	s_waitcnt lgkmcnt(0)
	s_barrier
	s_setprio 1
	ds_read_b128 v[212:215], v116 offset:36864
	ds_read_b128 v[216:219], v115
	ds_read_b128 v[220:223], v115 offset:4608
	ds_read_b128 v[224:227], v116 offset:36896
	ds_read_b128 v[228:231], v115 offset:32
	ds_read_b128 v[244:247], v115 offset:4640
	ds_read_b128 v[252:255], v116 offset:36928
	s_waitcnt lgkmcnt(5)
	v_mfma_f32_32x32x16_bf16 v[0:15], v[212:215], v[216:219], v[0:15]
	ds_read_b128 v[216:219], v115 offset:64
	s_waitcnt lgkmcnt(5)
	v_mfma_f32_32x32x16_bf16 v[16:31], v[212:215], v[220:223], v[16:31]
	ds_read_b128 v[212:215], v115 offset:4672
	ds_read_b128 v[220:223], v116 offset:36960
	s_waitcnt lgkmcnt(5)
	v_mfma_f32_32x32x16_bf16 v[0:15], v[224:227], v[228:231], v[0:15]
	ds_read_b128 v[228:231], v115 offset:96
	s_waitcnt lgkmcnt(5)
	v_mfma_f32_32x32x16_bf16 v[16:31], v[224:227], v[244:247], v[16:31]
	ds_read_b128 v[224:227], v115 offset:4704
	s_waitcnt lgkmcnt(4)
	v_mfma_f32_32x32x16_bf16 v[0:15], v[252:255], v[216:219], v[0:15]
	s_waitcnt lgkmcnt(3)
	v_mfma_f32_32x32x16_bf16 v[16:31], v[252:255], v[212:215], v[16:31]
	s_waitcnt lgkmcnt(1)
	v_mfma_f32_32x32x16_bf16 v[0:15], v[220:223], v[228:231], v[0:15]
	s_waitcnt lgkmcnt(0)
	v_mfma_f32_32x32x16_bf16 v[16:31], v[220:223], v[224:227], v[16:31]
	s_waitcnt vmcnt(11)
	ds_write_b128 v96, v[36:39] offset:18432
	global_load_dwordx4 v[36:39], v[104:105], off offset:1920
	s_waitcnt vmcnt(11)
	ds_write_b128 v96, v[52:55] offset:23040
	global_load_dwordx4 v[52:55], v[106:107], off offset:1920
	s_waitcnt vmcnt(11)
	ds_write_b128 v96, v[56:59] offset:27648
	global_load_dwordx4 v[56:59], v[108:109], off offset:1920
	s_waitcnt vmcnt(11)
	ds_write_b128 v96, v[60:63] offset:32256
	global_load_dwordx4 v[60:63], v[110:111], off offset:1920
	s_waitcnt vmcnt(11)
	ds_write_b128 v96, v[64:67] offset:55296
	global_load_dwordx4 v[64:67], v[102:103], off offset:1920
	s_waitcnt vmcnt(11)
	ds_write_b128 v96, v[72:75] offset:59904
	global_load_dwordx4 v[72:75], v[112:113], off offset:1920
	s_setprio 0
	s_waitcnt lgkmcnt(0)
	s_barrier
	s_setprio 1
	ds_read_b128 v[212:215], v116 offset:55296
	ds_read_b128 v[216:219], v115 offset:18432
	ds_read_b128 v[220:223], v115 offset:23040
	ds_read_b128 v[224:227], v116 offset:55328
	ds_read_b128 v[228:231], v115 offset:18464
	ds_read_b128 v[244:247], v115 offset:23072
	ds_read_b128 v[252:255], v116 offset:55360
	s_waitcnt lgkmcnt(5)
	v_mfma_f32_32x32x16_bf16 v[0:15], v[212:215], v[216:219], v[0:15]
	ds_read_b128 v[216:219], v115 offset:18496
	s_waitcnt lgkmcnt(5)
	v_mfma_f32_32x32x16_bf16 v[16:31], v[212:215], v[220:223], v[16:31]
	ds_read_b128 v[212:215], v115 offset:23104
	ds_read_b128 v[220:223], v116 offset:55392
	s_waitcnt lgkmcnt(5)
	v_mfma_f32_32x32x16_bf16 v[0:15], v[224:227], v[228:231], v[0:15]
	ds_read_b128 v[228:231], v115 offset:18528
	s_waitcnt lgkmcnt(5)
	v_mfma_f32_32x32x16_bf16 v[16:31], v[224:227], v[244:247], v[16:31]
	ds_read_b128 v[224:227], v115 offset:23136
	s_waitcnt lgkmcnt(4)
	v_mfma_f32_32x32x16_bf16 v[0:15], v[252:255], v[216:219], v[0:15]
	s_waitcnt lgkmcnt(3)
	v_mfma_f32_32x32x16_bf16 v[16:31], v[252:255], v[212:215], v[16:31]
	s_waitcnt lgkmcnt(1)
	v_mfma_f32_32x32x16_bf16 v[0:15], v[220:223], v[228:231], v[0:15]
	s_waitcnt lgkmcnt(0)
	v_mfma_f32_32x32x16_bf16 v[16:31], v[220:223], v[224:227], v[16:31]
	s_waitcnt vmcnt(11)
	ds_write_b128 v96, v[32:35]
	global_load_dwordx4 v[32:35], v[104:105], off offset:2048
	s_waitcnt vmcnt(11)
	ds_write_b128 v96, v[40:43] offset:4608
	global_load_dwordx4 v[40:43], v[106:107], off offset:2048
	s_waitcnt vmcnt(11)
	ds_write_b128 v96, v[44:47] offset:9216
	global_load_dwordx4 v[44:47], v[108:109], off offset:2048
	s_waitcnt vmcnt(11)
	ds_write_b128 v96, v[48:51] offset:13824
	global_load_dwordx4 v[48:51], v[110:111], off offset:2048
	s_waitcnt vmcnt(11)
	ds_write_b128 v96, v[68:71] offset:36864
	global_load_dwordx4 v[68:71], v[102:103], off offset:2048
	s_waitcnt vmcnt(11)
	ds_write_b128 v96, v[76:79] offset:41472
	global_load_dwordx4 v[76:79], v[112:113], off offset:2048
	s_setprio 0
	s_waitcnt lgkmcnt(0)
	s_barrier
	s_setprio 1
	ds_read_b128 v[212:215], v116 offset:36864
	ds_read_b128 v[216:219], v115
	ds_read_b128 v[220:223], v115 offset:4608
	ds_read_b128 v[224:227], v116 offset:36896
	ds_read_b128 v[228:231], v115 offset:32
	ds_read_b128 v[244:247], v115 offset:4640
	ds_read_b128 v[252:255], v116 offset:36928
	s_waitcnt lgkmcnt(5)
	v_mfma_f32_32x32x16_bf16 v[0:15], v[212:215], v[216:219], v[0:15]
	ds_read_b128 v[216:219], v115 offset:64
	s_waitcnt lgkmcnt(5)
	v_mfma_f32_32x32x16_bf16 v[16:31], v[212:215], v[220:223], v[16:31]
	ds_read_b128 v[212:215], v115 offset:4672
	ds_read_b128 v[220:223], v116 offset:36960
	s_waitcnt lgkmcnt(5)
	v_mfma_f32_32x32x16_bf16 v[0:15], v[224:227], v[228:231], v[0:15]
	ds_read_b128 v[228:231], v115 offset:96
	s_waitcnt lgkmcnt(5)
	v_mfma_f32_32x32x16_bf16 v[16:31], v[224:227], v[244:247], v[16:31]
	ds_read_b128 v[224:227], v115 offset:4704
	s_waitcnt lgkmcnt(4)
	v_mfma_f32_32x32x16_bf16 v[0:15], v[252:255], v[216:219], v[0:15]
	s_waitcnt lgkmcnt(3)
	v_mfma_f32_32x32x16_bf16 v[16:31], v[252:255], v[212:215], v[16:31]
	s_waitcnt lgkmcnt(1)
	v_mfma_f32_32x32x16_bf16 v[0:15], v[220:223], v[228:231], v[0:15]
	s_waitcnt lgkmcnt(0)
	v_mfma_f32_32x32x16_bf16 v[16:31], v[220:223], v[224:227], v[16:31]
	s_waitcnt vmcnt(11)
	ds_write_b128 v96, v[36:39] offset:18432
	global_load_dwordx4 v[36:39], v[104:105], off offset:2176
	s_waitcnt vmcnt(11)
	ds_write_b128 v96, v[52:55] offset:23040
	global_load_dwordx4 v[52:55], v[106:107], off offset:2176
	s_waitcnt vmcnt(11)
	ds_write_b128 v96, v[56:59] offset:27648
	global_load_dwordx4 v[56:59], v[108:109], off offset:2176
	s_waitcnt vmcnt(11)
	ds_write_b128 v96, v[60:63] offset:32256
	global_load_dwordx4 v[60:63], v[110:111], off offset:2176
	s_waitcnt vmcnt(11)
	ds_write_b128 v96, v[64:67] offset:55296
	global_load_dwordx4 v[64:67], v[102:103], off offset:2176
	s_waitcnt vmcnt(11)
	ds_write_b128 v96, v[72:75] offset:59904
	global_load_dwordx4 v[72:75], v[112:113], off offset:2176
	s_setprio 0
	s_waitcnt lgkmcnt(0)
	s_barrier
	s_setprio 1
	ds_read_b128 v[212:215], v116 offset:55296
	ds_read_b128 v[216:219], v115 offset:18432
	ds_read_b128 v[220:223], v115 offset:23040
	ds_read_b128 v[224:227], v116 offset:55328
	ds_read_b128 v[228:231], v115 offset:18464
	ds_read_b128 v[244:247], v115 offset:23072
	ds_read_b128 v[252:255], v116 offset:55360
	s_waitcnt lgkmcnt(5)
	v_mfma_f32_32x32x16_bf16 v[0:15], v[212:215], v[216:219], v[0:15]
	ds_read_b128 v[216:219], v115 offset:18496
	s_waitcnt lgkmcnt(5)
	v_mfma_f32_32x32x16_bf16 v[16:31], v[212:215], v[220:223], v[16:31]
	ds_read_b128 v[212:215], v115 offset:23104
	ds_read_b128 v[220:223], v116 offset:55392
	s_waitcnt lgkmcnt(5)
	v_mfma_f32_32x32x16_bf16 v[0:15], v[224:227], v[228:231], v[0:15]
	ds_read_b128 v[228:231], v115 offset:18528
	s_waitcnt lgkmcnt(5)
	v_mfma_f32_32x32x16_bf16 v[16:31], v[224:227], v[244:247], v[16:31]
	ds_read_b128 v[224:227], v115 offset:23136
	s_waitcnt lgkmcnt(4)
	v_mfma_f32_32x32x16_bf16 v[0:15], v[252:255], v[216:219], v[0:15]
	s_waitcnt lgkmcnt(3)
	v_mfma_f32_32x32x16_bf16 v[16:31], v[252:255], v[212:215], v[16:31]
	s_waitcnt lgkmcnt(1)
	v_mfma_f32_32x32x16_bf16 v[0:15], v[220:223], v[228:231], v[0:15]
	s_waitcnt lgkmcnt(0)
	v_mfma_f32_32x32x16_bf16 v[16:31], v[220:223], v[224:227], v[16:31]
	s_waitcnt vmcnt(11)
	ds_write_b128 v96, v[32:35]
	global_load_dwordx4 v[32:35], v[104:105], off offset:2304
	s_waitcnt vmcnt(11)
	ds_write_b128 v96, v[40:43] offset:4608
	global_load_dwordx4 v[40:43], v[106:107], off offset:2304
	s_waitcnt vmcnt(11)
	ds_write_b128 v96, v[44:47] offset:9216
	global_load_dwordx4 v[44:47], v[108:109], off offset:2304
	s_waitcnt vmcnt(11)
	ds_write_b128 v96, v[48:51] offset:13824
	global_load_dwordx4 v[48:51], v[110:111], off offset:2304
	s_waitcnt vmcnt(11)
	ds_write_b128 v96, v[68:71] offset:36864
	global_load_dwordx4 v[68:71], v[102:103], off offset:2304
	s_waitcnt vmcnt(11)
	ds_write_b128 v96, v[76:79] offset:41472
	global_load_dwordx4 v[76:79], v[112:113], off offset:2304
	s_setprio 0
	s_waitcnt lgkmcnt(0)
	s_barrier
	s_setprio 1
	ds_read_b128 v[212:215], v116 offset:36864
	ds_read_b128 v[216:219], v115
	ds_read_b128 v[220:223], v115 offset:4608
	ds_read_b128 v[224:227], v116 offset:36896
	ds_read_b128 v[228:231], v115 offset:32
	ds_read_b128 v[244:247], v115 offset:4640
	ds_read_b128 v[252:255], v116 offset:36928
	s_waitcnt lgkmcnt(5)
	v_mfma_f32_32x32x16_bf16 v[0:15], v[212:215], v[216:219], v[0:15]
	ds_read_b128 v[216:219], v115 offset:64
	s_waitcnt lgkmcnt(5)
	v_mfma_f32_32x32x16_bf16 v[16:31], v[212:215], v[220:223], v[16:31]
	ds_read_b128 v[212:215], v115 offset:4672
	ds_read_b128 v[220:223], v116 offset:36960
	s_waitcnt lgkmcnt(5)
	v_mfma_f32_32x32x16_bf16 v[0:15], v[224:227], v[228:231], v[0:15]
	ds_read_b128 v[228:231], v115 offset:96
	s_waitcnt lgkmcnt(5)
	v_mfma_f32_32x32x16_bf16 v[16:31], v[224:227], v[244:247], v[16:31]
	ds_read_b128 v[224:227], v115 offset:4704
	s_waitcnt lgkmcnt(4)
	v_mfma_f32_32x32x16_bf16 v[0:15], v[252:255], v[216:219], v[0:15]
	s_waitcnt lgkmcnt(3)
	v_mfma_f32_32x32x16_bf16 v[16:31], v[252:255], v[212:215], v[16:31]
	s_waitcnt lgkmcnt(1)
	v_mfma_f32_32x32x16_bf16 v[0:15], v[220:223], v[228:231], v[0:15]
	s_waitcnt lgkmcnt(0)
	v_mfma_f32_32x32x16_bf16 v[16:31], v[220:223], v[224:227], v[16:31]
	s_waitcnt vmcnt(11)
	ds_write_b128 v96, v[36:39] offset:18432
	global_load_dwordx4 v[36:39], v[104:105], off offset:2432
	s_waitcnt vmcnt(11)
	ds_write_b128 v96, v[52:55] offset:23040
	global_load_dwordx4 v[52:55], v[106:107], off offset:2432
	s_waitcnt vmcnt(11)
	ds_write_b128 v96, v[56:59] offset:27648
	global_load_dwordx4 v[56:59], v[108:109], off offset:2432
	s_waitcnt vmcnt(11)
	ds_write_b128 v96, v[60:63] offset:32256
	global_load_dwordx4 v[60:63], v[110:111], off offset:2432
	s_waitcnt vmcnt(11)
	ds_write_b128 v96, v[64:67] offset:55296
	global_load_dwordx4 v[64:67], v[102:103], off offset:2432
	s_waitcnt vmcnt(11)
	ds_write_b128 v96, v[72:75] offset:59904
	global_load_dwordx4 v[72:75], v[112:113], off offset:2432
	s_setprio 0
	s_waitcnt lgkmcnt(0)
	s_barrier
	s_setprio 1
	ds_read_b128 v[212:215], v116 offset:55296
	ds_read_b128 v[216:219], v115 offset:18432
	ds_read_b128 v[220:223], v115 offset:23040
	ds_read_b128 v[224:227], v116 offset:55328
	ds_read_b128 v[228:231], v115 offset:18464
	ds_read_b128 v[244:247], v115 offset:23072
	ds_read_b128 v[252:255], v116 offset:55360
	s_waitcnt lgkmcnt(5)
	v_mfma_f32_32x32x16_bf16 v[0:15], v[212:215], v[216:219], v[0:15]
	ds_read_b128 v[216:219], v115 offset:18496
	s_waitcnt lgkmcnt(5)
	v_mfma_f32_32x32x16_bf16 v[16:31], v[212:215], v[220:223], v[16:31]
	ds_read_b128 v[212:215], v115 offset:23104
	ds_read_b128 v[220:223], v116 offset:55392
	s_waitcnt lgkmcnt(5)
	v_mfma_f32_32x32x16_bf16 v[0:15], v[224:227], v[228:231], v[0:15]
	ds_read_b128 v[228:231], v115 offset:18528
	s_waitcnt lgkmcnt(5)
	v_mfma_f32_32x32x16_bf16 v[16:31], v[224:227], v[244:247], v[16:31]
	ds_read_b128 v[224:227], v115 offset:23136
	s_waitcnt lgkmcnt(4)
	v_mfma_f32_32x32x16_bf16 v[0:15], v[252:255], v[216:219], v[0:15]
	s_waitcnt lgkmcnt(3)
	v_mfma_f32_32x32x16_bf16 v[16:31], v[252:255], v[212:215], v[16:31]
	s_waitcnt lgkmcnt(1)
	v_mfma_f32_32x32x16_bf16 v[0:15], v[220:223], v[228:231], v[0:15]
	s_waitcnt lgkmcnt(0)
	v_mfma_f32_32x32x16_bf16 v[16:31], v[220:223], v[224:227], v[16:31]
	s_waitcnt vmcnt(11)
	ds_write_b128 v96, v[32:35]
	global_load_dwordx4 v[32:35], v[104:105], off offset:2560
	s_waitcnt vmcnt(11)
	ds_write_b128 v96, v[40:43] offset:4608
	global_load_dwordx4 v[40:43], v[106:107], off offset:2560
	s_waitcnt vmcnt(11)
	ds_write_b128 v96, v[44:47] offset:9216
	global_load_dwordx4 v[44:47], v[108:109], off offset:2560
	s_waitcnt vmcnt(11)
	ds_write_b128 v96, v[48:51] offset:13824
	global_load_dwordx4 v[48:51], v[110:111], off offset:2560
	s_waitcnt vmcnt(11)
	ds_write_b128 v96, v[68:71] offset:36864
	global_load_dwordx4 v[68:71], v[102:103], off offset:2560
	s_waitcnt vmcnt(11)
	ds_write_b128 v96, v[76:79] offset:41472
	global_load_dwordx4 v[76:79], v[112:113], off offset:2560
	s_setprio 0
	s_waitcnt lgkmcnt(0)
	s_barrier
	s_setprio 1
	ds_read_b128 v[212:215], v116 offset:36864
	ds_read_b128 v[216:219], v115
	ds_read_b128 v[220:223], v115 offset:4608
	ds_read_b128 v[224:227], v116 offset:36896
	ds_read_b128 v[228:231], v115 offset:32
	ds_read_b128 v[244:247], v115 offset:4640
	ds_read_b128 v[252:255], v116 offset:36928
	s_waitcnt lgkmcnt(5)
	v_mfma_f32_32x32x16_bf16 v[0:15], v[212:215], v[216:219], v[0:15]
	ds_read_b128 v[216:219], v115 offset:64
	s_waitcnt lgkmcnt(5)
	v_mfma_f32_32x32x16_bf16 v[16:31], v[212:215], v[220:223], v[16:31]
	ds_read_b128 v[212:215], v115 offset:4672
	ds_read_b128 v[220:223], v116 offset:36960
	s_waitcnt lgkmcnt(5)
	v_mfma_f32_32x32x16_bf16 v[0:15], v[224:227], v[228:231], v[0:15]
	ds_read_b128 v[228:231], v115 offset:96
	s_waitcnt lgkmcnt(5)
	v_mfma_f32_32x32x16_bf16 v[16:31], v[224:227], v[244:247], v[16:31]
	ds_read_b128 v[224:227], v115 offset:4704
	s_waitcnt lgkmcnt(4)
	v_mfma_f32_32x32x16_bf16 v[0:15], v[252:255], v[216:219], v[0:15]
	s_waitcnt lgkmcnt(3)
	v_mfma_f32_32x32x16_bf16 v[16:31], v[252:255], v[212:215], v[16:31]
	s_waitcnt lgkmcnt(1)
	v_mfma_f32_32x32x16_bf16 v[0:15], v[220:223], v[228:231], v[0:15]
	s_waitcnt lgkmcnt(0)
	v_mfma_f32_32x32x16_bf16 v[16:31], v[220:223], v[224:227], v[16:31]
	s_waitcnt vmcnt(11)
	ds_write_b128 v96, v[36:39] offset:18432
	global_load_dwordx4 v[36:39], v[104:105], off offset:2688
	s_waitcnt vmcnt(11)
	ds_write_b128 v96, v[52:55] offset:23040
	global_load_dwordx4 v[52:55], v[106:107], off offset:2688
	s_waitcnt vmcnt(11)
	ds_write_b128 v96, v[56:59] offset:27648
	global_load_dwordx4 v[56:59], v[108:109], off offset:2688
	s_waitcnt vmcnt(11)
	ds_write_b128 v96, v[60:63] offset:32256
	global_load_dwordx4 v[60:63], v[110:111], off offset:2688
	s_waitcnt vmcnt(11)
	ds_write_b128 v96, v[64:67] offset:55296
	global_load_dwordx4 v[64:67], v[102:103], off offset:2688
	s_waitcnt vmcnt(11)
	ds_write_b128 v96, v[72:75] offset:59904
	global_load_dwordx4 v[72:75], v[112:113], off offset:2688
	s_setprio 0
	s_waitcnt lgkmcnt(0)
	s_barrier
	s_setprio 1
	ds_read_b128 v[212:215], v116 offset:55296
	ds_read_b128 v[216:219], v115 offset:18432
	ds_read_b128 v[220:223], v115 offset:23040
	ds_read_b128 v[224:227], v116 offset:55328
	ds_read_b128 v[228:231], v115 offset:18464
	ds_read_b128 v[244:247], v115 offset:23072
	ds_read_b128 v[252:255], v116 offset:55360
	s_waitcnt lgkmcnt(5)
	v_mfma_f32_32x32x16_bf16 v[0:15], v[212:215], v[216:219], v[0:15]
	ds_read_b128 v[216:219], v115 offset:18496
	s_waitcnt lgkmcnt(5)
	v_mfma_f32_32x32x16_bf16 v[16:31], v[212:215], v[220:223], v[16:31]
	ds_read_b128 v[212:215], v115 offset:23104
	ds_read_b128 v[220:223], v116 offset:55392
	s_waitcnt lgkmcnt(5)
	v_mfma_f32_32x32x16_bf16 v[0:15], v[224:227], v[228:231], v[0:15]
	ds_read_b128 v[228:231], v115 offset:18528
	s_waitcnt lgkmcnt(5)
	v_mfma_f32_32x32x16_bf16 v[16:31], v[224:227], v[244:247], v[16:31]
	ds_read_b128 v[224:227], v115 offset:23136
	s_waitcnt lgkmcnt(4)
	v_mfma_f32_32x32x16_bf16 v[0:15], v[252:255], v[216:219], v[0:15]
	s_waitcnt lgkmcnt(3)
	v_mfma_f32_32x32x16_bf16 v[16:31], v[252:255], v[212:215], v[16:31]
	s_waitcnt lgkmcnt(1)
	v_mfma_f32_32x32x16_bf16 v[0:15], v[220:223], v[228:231], v[0:15]
	s_waitcnt lgkmcnt(0)
	v_mfma_f32_32x32x16_bf16 v[16:31], v[220:223], v[224:227], v[16:31]
	s_waitcnt vmcnt(11)
	ds_write_b128 v96, v[32:35]
	global_load_dwordx4 v[32:35], v[104:105], off offset:2816
	s_waitcnt vmcnt(11)
	ds_write_b128 v96, v[40:43] offset:4608
	global_load_dwordx4 v[40:43], v[106:107], off offset:2816
	s_waitcnt vmcnt(11)
	ds_write_b128 v96, v[44:47] offset:9216
	global_load_dwordx4 v[44:47], v[108:109], off offset:2816
	s_waitcnt vmcnt(11)
	ds_write_b128 v96, v[48:51] offset:13824
	global_load_dwordx4 v[48:51], v[110:111], off offset:2816
	s_waitcnt vmcnt(11)
	ds_write_b128 v96, v[68:71] offset:36864
	global_load_dwordx4 v[68:71], v[102:103], off offset:2816
	s_waitcnt vmcnt(11)
	ds_write_b128 v96, v[76:79] offset:41472
	global_load_dwordx4 v[76:79], v[112:113], off offset:2816
	s_setprio 0
	s_waitcnt lgkmcnt(0)
	s_barrier
	s_setprio 1
	ds_read_b128 v[212:215], v116 offset:36864
	ds_read_b128 v[216:219], v115
	ds_read_b128 v[220:223], v115 offset:4608
	ds_read_b128 v[224:227], v116 offset:36896
	ds_read_b128 v[228:231], v115 offset:32
	ds_read_b128 v[244:247], v115 offset:4640
	ds_read_b128 v[252:255], v116 offset:36928
	s_waitcnt lgkmcnt(5)
	v_mfma_f32_32x32x16_bf16 v[0:15], v[212:215], v[216:219], v[0:15]
	ds_read_b128 v[216:219], v115 offset:64
	s_waitcnt lgkmcnt(5)
	v_mfma_f32_32x32x16_bf16 v[16:31], v[212:215], v[220:223], v[16:31]
	ds_read_b128 v[212:215], v115 offset:4672
	ds_read_b128 v[220:223], v116 offset:36960
	s_waitcnt lgkmcnt(5)
	v_mfma_f32_32x32x16_bf16 v[0:15], v[224:227], v[228:231], v[0:15]
	ds_read_b128 v[228:231], v115 offset:96
	s_waitcnt lgkmcnt(5)
	v_mfma_f32_32x32x16_bf16 v[16:31], v[224:227], v[244:247], v[16:31]
	ds_read_b128 v[224:227], v115 offset:4704
	s_waitcnt lgkmcnt(4)
	v_mfma_f32_32x32x16_bf16 v[0:15], v[252:255], v[216:219], v[0:15]
	s_waitcnt lgkmcnt(3)
	v_mfma_f32_32x32x16_bf16 v[16:31], v[252:255], v[212:215], v[16:31]
	s_waitcnt lgkmcnt(1)
	v_mfma_f32_32x32x16_bf16 v[0:15], v[220:223], v[228:231], v[0:15]
	s_waitcnt lgkmcnt(0)
	v_mfma_f32_32x32x16_bf16 v[16:31], v[220:223], v[224:227], v[16:31]
	s_waitcnt vmcnt(11)
	ds_write_b128 v96, v[36:39] offset:18432
	global_load_dwordx4 v[36:39], v[104:105], off offset:2944
	s_waitcnt vmcnt(11)
	ds_write_b128 v96, v[52:55] offset:23040
	global_load_dwordx4 v[52:55], v[106:107], off offset:2944
	s_waitcnt vmcnt(11)
	ds_write_b128 v96, v[56:59] offset:27648
	global_load_dwordx4 v[56:59], v[108:109], off offset:2944
	s_waitcnt vmcnt(11)
	ds_write_b128 v96, v[60:63] offset:32256
	global_load_dwordx4 v[60:63], v[110:111], off offset:2944
	s_waitcnt vmcnt(11)
	ds_write_b128 v96, v[64:67] offset:55296
	global_load_dwordx4 v[64:67], v[102:103], off offset:2944
	s_waitcnt vmcnt(11)
	ds_write_b128 v96, v[72:75] offset:59904
	global_load_dwordx4 v[72:75], v[112:113], off offset:2944
	s_setprio 0
	s_waitcnt lgkmcnt(0)
	s_barrier
	s_setprio 1
	ds_read_b128 v[212:215], v116 offset:55296
	ds_read_b128 v[216:219], v115 offset:18432
	ds_read_b128 v[220:223], v115 offset:23040
	ds_read_b128 v[224:227], v116 offset:55328
	ds_read_b128 v[228:231], v115 offset:18464
	ds_read_b128 v[244:247], v115 offset:23072
	ds_read_b128 v[252:255], v116 offset:55360
	s_waitcnt lgkmcnt(5)
	v_mfma_f32_32x32x16_bf16 v[0:15], v[212:215], v[216:219], v[0:15]
	ds_read_b128 v[216:219], v115 offset:18496
	s_waitcnt lgkmcnt(5)
	v_mfma_f32_32x32x16_bf16 v[16:31], v[212:215], v[220:223], v[16:31]
	ds_read_b128 v[212:215], v115 offset:23104
	ds_read_b128 v[220:223], v116 offset:55392
	s_waitcnt lgkmcnt(5)
	v_mfma_f32_32x32x16_bf16 v[0:15], v[224:227], v[228:231], v[0:15]
	ds_read_b128 v[228:231], v115 offset:18528
	s_waitcnt lgkmcnt(5)
	v_mfma_f32_32x32x16_bf16 v[16:31], v[224:227], v[244:247], v[16:31]
	ds_read_b128 v[224:227], v115 offset:23136
	s_waitcnt lgkmcnt(4)
	v_mfma_f32_32x32x16_bf16 v[0:15], v[252:255], v[216:219], v[0:15]
	s_waitcnt lgkmcnt(3)
	v_mfma_f32_32x32x16_bf16 v[16:31], v[252:255], v[212:215], v[16:31]
	s_waitcnt lgkmcnt(1)
	v_mfma_f32_32x32x16_bf16 v[0:15], v[220:223], v[228:231], v[0:15]
	s_waitcnt lgkmcnt(0)
	v_mfma_f32_32x32x16_bf16 v[16:31], v[220:223], v[224:227], v[16:31]
	s_waitcnt vmcnt(11)
	ds_write_b128 v96, v[32:35]
	global_load_dwordx4 v[32:35], v[104:105], off offset:3072
	s_waitcnt vmcnt(11)
	ds_write_b128 v96, v[40:43] offset:4608
	global_load_dwordx4 v[40:43], v[106:107], off offset:3072
	s_waitcnt vmcnt(11)
	ds_write_b128 v96, v[44:47] offset:9216
	global_load_dwordx4 v[44:47], v[108:109], off offset:3072
	s_waitcnt vmcnt(11)
	ds_write_b128 v96, v[48:51] offset:13824
	global_load_dwordx4 v[48:51], v[110:111], off offset:3072
	s_waitcnt vmcnt(11)
	ds_write_b128 v96, v[68:71] offset:36864
	global_load_dwordx4 v[68:71], v[102:103], off offset:3072
	s_waitcnt vmcnt(11)
	ds_write_b128 v96, v[76:79] offset:41472
	global_load_dwordx4 v[76:79], v[112:113], off offset:3072
	s_setprio 0
	s_waitcnt lgkmcnt(0)
	s_barrier
	s_setprio 1
	ds_read_b128 v[212:215], v116 offset:36864
	ds_read_b128 v[216:219], v115
	ds_read_b128 v[220:223], v115 offset:4608
	ds_read_b128 v[224:227], v116 offset:36896
	ds_read_b128 v[228:231], v115 offset:32
	ds_read_b128 v[244:247], v115 offset:4640
	ds_read_b128 v[252:255], v116 offset:36928
	s_waitcnt lgkmcnt(5)
	v_mfma_f32_32x32x16_bf16 v[0:15], v[212:215], v[216:219], v[0:15]
	ds_read_b128 v[216:219], v115 offset:64
	s_waitcnt lgkmcnt(5)
	v_mfma_f32_32x32x16_bf16 v[16:31], v[212:215], v[220:223], v[16:31]
	ds_read_b128 v[212:215], v115 offset:4672
	ds_read_b128 v[220:223], v116 offset:36960
	s_waitcnt lgkmcnt(5)
	v_mfma_f32_32x32x16_bf16 v[0:15], v[224:227], v[228:231], v[0:15]
	ds_read_b128 v[228:231], v115 offset:96
	s_waitcnt lgkmcnt(5)
	v_mfma_f32_32x32x16_bf16 v[16:31], v[224:227], v[244:247], v[16:31]
	ds_read_b128 v[224:227], v115 offset:4704
	s_waitcnt lgkmcnt(4)
	v_mfma_f32_32x32x16_bf16 v[0:15], v[252:255], v[216:219], v[0:15]
	s_waitcnt lgkmcnt(3)
	v_mfma_f32_32x32x16_bf16 v[16:31], v[252:255], v[212:215], v[16:31]
	s_waitcnt lgkmcnt(1)
	v_mfma_f32_32x32x16_bf16 v[0:15], v[220:223], v[228:231], v[0:15]
	s_waitcnt lgkmcnt(0)
	v_mfma_f32_32x32x16_bf16 v[16:31], v[220:223], v[224:227], v[16:31]
	s_waitcnt vmcnt(11)
	ds_write_b128 v96, v[36:39] offset:18432
	global_load_dwordx4 v[36:39], v[104:105], off offset:3200
	s_waitcnt vmcnt(11)
	ds_write_b128 v96, v[52:55] offset:23040
	global_load_dwordx4 v[52:55], v[106:107], off offset:3200
	s_waitcnt vmcnt(11)
	ds_write_b128 v96, v[56:59] offset:27648
	global_load_dwordx4 v[56:59], v[108:109], off offset:3200
	s_waitcnt vmcnt(11)
	ds_write_b128 v96, v[60:63] offset:32256
	global_load_dwordx4 v[60:63], v[110:111], off offset:3200
	s_waitcnt vmcnt(11)
	ds_write_b128 v96, v[64:67] offset:55296
	global_load_dwordx4 v[64:67], v[102:103], off offset:3200
	s_waitcnt vmcnt(11)
	ds_write_b128 v96, v[72:75] offset:59904
	global_load_dwordx4 v[72:75], v[112:113], off offset:3200
	s_setprio 0
	s_waitcnt lgkmcnt(0)
	s_barrier
	s_setprio 1
	ds_read_b128 v[212:215], v116 offset:55296
	ds_read_b128 v[216:219], v115 offset:18432
	ds_read_b128 v[220:223], v115 offset:23040
	ds_read_b128 v[224:227], v116 offset:55328
	ds_read_b128 v[228:231], v115 offset:18464
	ds_read_b128 v[244:247], v115 offset:23072
	ds_read_b128 v[252:255], v116 offset:55360
	s_waitcnt lgkmcnt(5)
	v_mfma_f32_32x32x16_bf16 v[0:15], v[212:215], v[216:219], v[0:15]
	ds_read_b128 v[216:219], v115 offset:18496
	s_waitcnt lgkmcnt(5)
	v_mfma_f32_32x32x16_bf16 v[16:31], v[212:215], v[220:223], v[16:31]
	ds_read_b128 v[212:215], v115 offset:23104
	ds_read_b128 v[220:223], v116 offset:55392
	s_waitcnt lgkmcnt(5)
	v_mfma_f32_32x32x16_bf16 v[0:15], v[224:227], v[228:231], v[0:15]
	ds_read_b128 v[228:231], v115 offset:18528
	s_waitcnt lgkmcnt(5)
	v_mfma_f32_32x32x16_bf16 v[16:31], v[224:227], v[244:247], v[16:31]
	ds_read_b128 v[224:227], v115 offset:23136
	s_waitcnt lgkmcnt(4)
	v_mfma_f32_32x32x16_bf16 v[0:15], v[252:255], v[216:219], v[0:15]
	s_waitcnt lgkmcnt(3)
	v_mfma_f32_32x32x16_bf16 v[16:31], v[252:255], v[212:215], v[16:31]
	s_waitcnt lgkmcnt(1)
	v_mfma_f32_32x32x16_bf16 v[0:15], v[220:223], v[228:231], v[0:15]
	s_waitcnt lgkmcnt(0)
	v_mfma_f32_32x32x16_bf16 v[16:31], v[220:223], v[224:227], v[16:31]
	s_waitcnt vmcnt(11)
	ds_write_b128 v96, v[32:35]
	global_load_dwordx4 v[32:35], v[104:105], off offset:3328
	s_waitcnt vmcnt(11)
	ds_write_b128 v96, v[40:43] offset:4608
	global_load_dwordx4 v[40:43], v[106:107], off offset:3328
	s_waitcnt vmcnt(11)
	ds_write_b128 v96, v[44:47] offset:9216
	global_load_dwordx4 v[44:47], v[108:109], off offset:3328
	s_waitcnt vmcnt(11)
	ds_write_b128 v96, v[48:51] offset:13824
	global_load_dwordx4 v[48:51], v[110:111], off offset:3328
	s_waitcnt vmcnt(11)
	ds_write_b128 v96, v[68:71] offset:36864
	global_load_dwordx4 v[68:71], v[102:103], off offset:3328
	s_waitcnt vmcnt(11)
	ds_write_b128 v96, v[76:79] offset:41472
	global_load_dwordx4 v[76:79], v[112:113], off offset:3328
	s_setprio 0
	s_waitcnt lgkmcnt(0)
	s_barrier
	s_setprio 1
	ds_read_b128 v[212:215], v116 offset:36864
	ds_read_b128 v[216:219], v115
	ds_read_b128 v[220:223], v115 offset:4608
	ds_read_b128 v[224:227], v116 offset:36896
	ds_read_b128 v[228:231], v115 offset:32
	ds_read_b128 v[244:247], v115 offset:4640
	ds_read_b128 v[252:255], v116 offset:36928
	s_waitcnt lgkmcnt(5)
	v_mfma_f32_32x32x16_bf16 v[0:15], v[212:215], v[216:219], v[0:15]
	ds_read_b128 v[216:219], v115 offset:64
	s_waitcnt lgkmcnt(5)
	v_mfma_f32_32x32x16_bf16 v[16:31], v[212:215], v[220:223], v[16:31]
	ds_read_b128 v[212:215], v115 offset:4672
	ds_read_b128 v[220:223], v116 offset:36960
	s_waitcnt lgkmcnt(5)
	v_mfma_f32_32x32x16_bf16 v[0:15], v[224:227], v[228:231], v[0:15]
	ds_read_b128 v[228:231], v115 offset:96
	s_waitcnt lgkmcnt(5)
	v_mfma_f32_32x32x16_bf16 v[16:31], v[224:227], v[244:247], v[16:31]
	ds_read_b128 v[224:227], v115 offset:4704
	s_waitcnt lgkmcnt(4)
	v_mfma_f32_32x32x16_bf16 v[0:15], v[252:255], v[216:219], v[0:15]
	s_waitcnt lgkmcnt(3)
	v_mfma_f32_32x32x16_bf16 v[16:31], v[252:255], v[212:215], v[16:31]
	s_waitcnt lgkmcnt(1)
	v_mfma_f32_32x32x16_bf16 v[0:15], v[220:223], v[228:231], v[0:15]
	s_waitcnt lgkmcnt(0)
	v_mfma_f32_32x32x16_bf16 v[16:31], v[220:223], v[224:227], v[16:31]
	s_waitcnt vmcnt(11)
	ds_write_b128 v96, v[36:39] offset:18432
	global_load_dwordx4 v[36:39], v[104:105], off offset:3456
	s_waitcnt vmcnt(11)
	ds_write_b128 v96, v[52:55] offset:23040
	global_load_dwordx4 v[52:55], v[106:107], off offset:3456
	s_waitcnt vmcnt(11)
	ds_write_b128 v96, v[56:59] offset:27648
	global_load_dwordx4 v[56:59], v[108:109], off offset:3456
	s_waitcnt vmcnt(11)
	ds_write_b128 v96, v[60:63] offset:32256
	global_load_dwordx4 v[60:63], v[110:111], off offset:3456
	s_waitcnt vmcnt(11)
	ds_write_b128 v96, v[64:67] offset:55296
	global_load_dwordx4 v[64:67], v[102:103], off offset:3456
	s_waitcnt vmcnt(11)
	ds_write_b128 v96, v[72:75] offset:59904
	global_load_dwordx4 v[72:75], v[112:113], off offset:3456
	s_setprio 0
	s_waitcnt lgkmcnt(0)
	s_barrier
	s_setprio 1
	ds_read_b128 v[212:215], v116 offset:55296
	ds_read_b128 v[216:219], v115 offset:18432
	ds_read_b128 v[220:223], v115 offset:23040
	ds_read_b128 v[224:227], v116 offset:55328
	ds_read_b128 v[228:231], v115 offset:18464
	ds_read_b128 v[244:247], v115 offset:23072
	ds_read_b128 v[252:255], v116 offset:55360
	s_waitcnt lgkmcnt(5)
	v_mfma_f32_32x32x16_bf16 v[0:15], v[212:215], v[216:219], v[0:15]
	ds_read_b128 v[216:219], v115 offset:18496
	s_waitcnt lgkmcnt(5)
	v_mfma_f32_32x32x16_bf16 v[16:31], v[212:215], v[220:223], v[16:31]
	ds_read_b128 v[212:215], v115 offset:23104
	ds_read_b128 v[220:223], v116 offset:55392
	s_waitcnt lgkmcnt(5)
	v_mfma_f32_32x32x16_bf16 v[0:15], v[224:227], v[228:231], v[0:15]
	ds_read_b128 v[228:231], v115 offset:18528
	s_waitcnt lgkmcnt(5)
	v_mfma_f32_32x32x16_bf16 v[16:31], v[224:227], v[244:247], v[16:31]
	ds_read_b128 v[224:227], v115 offset:23136
	s_waitcnt lgkmcnt(4)
	v_mfma_f32_32x32x16_bf16 v[0:15], v[252:255], v[216:219], v[0:15]
	s_waitcnt lgkmcnt(3)
	v_mfma_f32_32x32x16_bf16 v[16:31], v[252:255], v[212:215], v[16:31]
	s_waitcnt lgkmcnt(1)
	v_mfma_f32_32x32x16_bf16 v[0:15], v[220:223], v[228:231], v[0:15]
	s_waitcnt lgkmcnt(0)
	v_mfma_f32_32x32x16_bf16 v[16:31], v[220:223], v[224:227], v[16:31]
	s_waitcnt vmcnt(11)
	ds_write_b128 v96, v[32:35]
	global_load_dwordx4 v[32:35], v[104:105], off offset:3584
	s_waitcnt vmcnt(11)
	ds_write_b128 v96, v[40:43] offset:4608
	global_load_dwordx4 v[40:43], v[106:107], off offset:3584
	s_waitcnt vmcnt(11)
	ds_write_b128 v96, v[44:47] offset:9216
	global_load_dwordx4 v[44:47], v[108:109], off offset:3584
	s_waitcnt vmcnt(11)
	ds_write_b128 v96, v[48:51] offset:13824
	global_load_dwordx4 v[48:51], v[110:111], off offset:3584
	s_waitcnt vmcnt(11)
	ds_write_b128 v96, v[68:71] offset:36864
	global_load_dwordx4 v[68:71], v[102:103], off offset:3584
	s_waitcnt vmcnt(11)
	ds_write_b128 v96, v[76:79] offset:41472
	global_load_dwordx4 v[76:79], v[112:113], off offset:3584
	s_setprio 0
	s_waitcnt lgkmcnt(0)
	s_barrier
	s_setprio 1
	ds_read_b128 v[212:215], v116 offset:36864
	ds_read_b128 v[216:219], v115
	ds_read_b128 v[220:223], v115 offset:4608
	ds_read_b128 v[224:227], v116 offset:36896
	ds_read_b128 v[228:231], v115 offset:32
	ds_read_b128 v[244:247], v115 offset:4640
	ds_read_b128 v[252:255], v116 offset:36928
	s_waitcnt lgkmcnt(5)
	v_mfma_f32_32x32x16_bf16 v[0:15], v[212:215], v[216:219], v[0:15]
	ds_read_b128 v[216:219], v115 offset:64
	s_waitcnt lgkmcnt(5)
	v_mfma_f32_32x32x16_bf16 v[16:31], v[212:215], v[220:223], v[16:31]
	ds_read_b128 v[212:215], v115 offset:4672
	ds_read_b128 v[220:223], v116 offset:36960
	s_waitcnt lgkmcnt(5)
	v_mfma_f32_32x32x16_bf16 v[0:15], v[224:227], v[228:231], v[0:15]
	ds_read_b128 v[228:231], v115 offset:96
	s_waitcnt lgkmcnt(5)
	v_mfma_f32_32x32x16_bf16 v[16:31], v[224:227], v[244:247], v[16:31]
	ds_read_b128 v[224:227], v115 offset:4704
	s_waitcnt lgkmcnt(4)
	v_mfma_f32_32x32x16_bf16 v[0:15], v[252:255], v[216:219], v[0:15]
	s_waitcnt lgkmcnt(3)
	v_mfma_f32_32x32x16_bf16 v[16:31], v[252:255], v[212:215], v[16:31]
	s_waitcnt lgkmcnt(1)
	v_mfma_f32_32x32x16_bf16 v[0:15], v[220:223], v[228:231], v[0:15]
	s_waitcnt lgkmcnt(0)
	v_mfma_f32_32x32x16_bf16 v[16:31], v[220:223], v[224:227], v[16:31]
	s_waitcnt vmcnt(11)
	ds_write_b128 v96, v[36:39] offset:18432
	global_load_dwordx4 v[36:39], v[104:105], off offset:3712
	s_waitcnt vmcnt(11)
	ds_write_b128 v96, v[52:55] offset:23040
	global_load_dwordx4 v[52:55], v[106:107], off offset:3712
	s_waitcnt vmcnt(11)
	ds_write_b128 v96, v[56:59] offset:27648
	global_load_dwordx4 v[56:59], v[108:109], off offset:3712
	s_waitcnt vmcnt(11)
	ds_write_b128 v96, v[60:63] offset:32256
	global_load_dwordx4 v[60:63], v[110:111], off offset:3712
	s_waitcnt vmcnt(11)
	ds_write_b128 v96, v[64:67] offset:55296
	global_load_dwordx4 v[64:67], v[102:103], off offset:3712
	s_waitcnt vmcnt(11)
	ds_write_b128 v96, v[72:75] offset:59904
	global_load_dwordx4 v[80:83], v[112:113], off offset:3712
	s_setprio 0
	s_waitcnt lgkmcnt(0)
	s_barrier
	s_setprio 1
	ds_read_b128 v[212:215], v116 offset:55296
	ds_read_b128 v[216:219], v115 offset:18432
	ds_read_b128 v[220:223], v115 offset:23040
	ds_read_b128 v[224:227], v116 offset:55328
	ds_read_b128 v[228:231], v115 offset:18464
	ds_read_b128 v[244:247], v115 offset:23072
	ds_read_b128 v[252:255], v116 offset:55360
	s_waitcnt lgkmcnt(5)
	v_mfma_f32_32x32x16_bf16 v[0:15], v[212:215], v[216:219], v[0:15]
	ds_read_b128 v[216:219], v115 offset:18496
	s_waitcnt lgkmcnt(5)
	v_mfma_f32_32x32x16_bf16 v[16:31], v[212:215], v[220:223], v[16:31]
	ds_read_b128 v[212:215], v115 offset:23104
	ds_read_b128 v[220:223], v116 offset:55392
	s_waitcnt lgkmcnt(5)
	v_mfma_f32_32x32x16_bf16 v[0:15], v[224:227], v[228:231], v[0:15]
	ds_read_b128 v[228:231], v115 offset:18528
	s_waitcnt lgkmcnt(5)
	v_mfma_f32_32x32x16_bf16 v[16:31], v[224:227], v[244:247], v[16:31]
	ds_read_b128 v[224:227], v115 offset:23136
	s_waitcnt lgkmcnt(4)
	v_mfma_f32_32x32x16_bf16 v[0:15], v[252:255], v[216:219], v[0:15]
	s_waitcnt lgkmcnt(3)
	v_mfma_f32_32x32x16_bf16 v[16:31], v[252:255], v[212:215], v[16:31]
	s_waitcnt lgkmcnt(1)
	v_mfma_f32_32x32x16_bf16 v[0:15], v[220:223], v[228:231], v[0:15]
	s_waitcnt lgkmcnt(0)
	v_mfma_f32_32x32x16_bf16 v[16:31], v[220:223], v[224:227], v[16:31]
	s_waitcnt vmcnt(11)
	ds_write_b128 v96, v[32:35]
	s_waitcnt vmcnt(10)
	ds_write_b128 v96, v[40:43] offset:4608
	global_load_dwordx4 v[40:43], v[104:105], off offset:3840
	s_waitcnt vmcnt(10)
	ds_write_b128 v96, v[44:47] offset:9216
	s_waitcnt vmcnt(9)
	ds_write_b128 v96, v[48:51] offset:13824
	s_waitcnt vmcnt(8)
	ds_write_b128 v96, v[68:71] offset:36864
	global_load_dwordx4 v[68:71], v[106:107], off offset:3840
	global_load_dwordx4 v[72:75], v[108:109], off offset:3840
	s_waitcnt vmcnt(9)
	ds_write_b128 v96, v[76:79] offset:41472
	global_load_dwordx4 v[76:79], v[110:111], off offset:3840
	global_load_dwordx4 v[84:87], v[102:103], off offset:3840
	global_load_dwordx4 v[88:91], v[112:113], off offset:3840
	s_setprio 0
	s_waitcnt lgkmcnt(0)
	s_barrier
	s_setprio 1
	ds_read_b128 v[212:215], v116 offset:36864
	ds_read_b128 v[216:219], v115
	ds_read_b128 v[220:223], v115 offset:4608
	ds_read_b128 v[224:227], v116 offset:36896
	ds_read_b128 v[228:231], v115 offset:32
	ds_read_b128 v[244:247], v115 offset:4640
	ds_read_b128 v[252:255], v116 offset:36928
	s_waitcnt lgkmcnt(5)
	v_mfma_f32_32x32x16_bf16 v[0:15], v[212:215], v[216:219], v[0:15]
	ds_read_b128 v[216:219], v115 offset:64
	s_waitcnt lgkmcnt(5)
	v_mfma_f32_32x32x16_bf16 v[16:31], v[212:215], v[220:223], v[16:31]
	ds_read_b128 v[212:215], v115 offset:4672
	ds_read_b128 v[220:223], v116 offset:36960
	s_waitcnt lgkmcnt(5)
	v_mfma_f32_32x32x16_bf16 v[0:15], v[224:227], v[228:231], v[0:15]
	ds_read_b128 v[228:231], v115 offset:96
	s_waitcnt lgkmcnt(5)
	v_mfma_f32_32x32x16_bf16 v[16:31], v[224:227], v[244:247], v[16:31]
	ds_read_b128 v[224:227], v115 offset:4704
	s_waitcnt lgkmcnt(4)
	v_mfma_f32_32x32x16_bf16 v[0:15], v[252:255], v[216:219], v[0:15]
	s_waitcnt lgkmcnt(3)
	v_mfma_f32_32x32x16_bf16 v[16:31], v[252:255], v[212:215], v[16:31]
	s_waitcnt lgkmcnt(1)
	v_mfma_f32_32x32x16_bf16 v[0:15], v[220:223], v[228:231], v[0:15]
	s_waitcnt lgkmcnt(0)
	v_mfma_f32_32x32x16_bf16 v[16:31], v[220:223], v[224:227], v[16:31]
	s_waitcnt vmcnt(11)
	ds_write_b128 v96, v[36:39] offset:18432
	global_load_dwordx4 v[32:35], v[104:105], off offset:3968
	s_waitcnt vmcnt(11)
	ds_write_b128 v96, v[52:55] offset:23040
	global_load_dwordx4 v[44:47], v[106:107], off offset:3968
	s_waitcnt vmcnt(11)
	ds_write_b128 v96, v[56:59] offset:27648
	global_load_dwordx4 v[48:51], v[108:109], off offset:3968
	s_waitcnt vmcnt(11)
	ds_write_b128 v96, v[60:63] offset:32256
	global_load_dwordx4 v[52:55], v[110:111], off offset:3968
	s_waitcnt vmcnt(11)
	ds_write_b128 v96, v[64:67] offset:55296
	global_load_dwordx4 v[64:67], v[102:103], off offset:3968
	s_waitcnt vmcnt(11)
	ds_write_b128 v96, v[80:83] offset:59904
	global_load_dwordx4 v[80:83], v[112:113], off offset:3968
	s_setprio 0
	s_waitcnt lgkmcnt(0)
	s_barrier
	s_setprio 1
	ds_read_b128 v[212:215], v116 offset:55296
	ds_read_b128 v[216:219], v115 offset:18432
	ds_read_b128 v[220:223], v115 offset:23040
	ds_read_b128 v[224:227], v116 offset:55328
	ds_read_b128 v[228:231], v115 offset:18464
	ds_read_b128 v[244:247], v115 offset:23072
	ds_read_b128 v[252:255], v116 offset:55360
	s_waitcnt lgkmcnt(5)
	v_mfma_f32_32x32x16_bf16 v[0:15], v[212:215], v[216:219], v[0:15]
	ds_read_b128 v[216:219], v115 offset:18496
	s_waitcnt lgkmcnt(5)
	v_mfma_f32_32x32x16_bf16 v[16:31], v[212:215], v[220:223], v[16:31]
	ds_read_b128 v[212:215], v115 offset:23104
	ds_read_b128 v[220:223], v116 offset:55392
	s_waitcnt lgkmcnt(5)
	v_mfma_f32_32x32x16_bf16 v[0:15], v[224:227], v[228:231], v[0:15]
	ds_read_b128 v[228:231], v115 offset:18528
	s_waitcnt lgkmcnt(5)
	v_mfma_f32_32x32x16_bf16 v[16:31], v[224:227], v[244:247], v[16:31]
	ds_read_b128 v[224:227], v115 offset:23136
	s_waitcnt lgkmcnt(4)
	v_mfma_f32_32x32x16_bf16 v[0:15], v[252:255], v[216:219], v[0:15]
	s_waitcnt lgkmcnt(3)
	v_mfma_f32_32x32x16_bf16 v[16:31], v[252:255], v[212:215], v[16:31]
	s_waitcnt lgkmcnt(1)
	v_mfma_f32_32x32x16_bf16 v[0:15], v[220:223], v[228:231], v[0:15]
	s_waitcnt lgkmcnt(0)
	v_mfma_f32_32x32x16_bf16 v[16:31], v[220:223], v[224:227], v[16:31]
	s_waitcnt vmcnt(11)
	ds_write_b128 v96, v[40:43]
	s_waitcnt vmcnt(10)
	ds_write_b128 v96, v[68:71] offset:4608
	s_waitcnt vmcnt(9)
	ds_write_b128 v96, v[72:75] offset:9216
	s_waitcnt vmcnt(8)
	ds_write_b128 v96, v[76:79] offset:13824
	s_waitcnt vmcnt(7)
	ds_write_b128 v96, v[84:87] offset:36864
	s_waitcnt vmcnt(6)
	ds_write_b128 v96, v[88:91] offset:41472
	v_add_co_u32_e32 v86, vcc, s9, v104
	s_nop 1
	v_addc_co_u32_e32 v87, vcc, 0, v105, vcc
	global_load_dwordx4 v[36:39], v[86:87], off
	global_load_dwordx4 v[40:43], v[92:93], off
	global_load_dwordx4 v[56:59], v[94:95], off
	global_load_dwordx4 v[60:63], v[98:99], off
	v_add_co_u32_e32 v84, vcc, s9, v102
	s_nop 1
	v_addc_co_u32_e32 v85, vcc, 0, v103, vcc
	global_load_dwordx4 v[68:71], v[84:85], off
	global_load_dwordx4 v[72:75], v[100:101], off
	s_setprio 0
	s_waitcnt lgkmcnt(0)
	s_barrier
	s_setprio 1
	ds_read_b128 v[212:215], v116 offset:36864
	ds_read_b128 v[216:219], v115
	ds_read_b128 v[220:223], v115 offset:4608
	ds_read_b128 v[224:227], v116 offset:36896
	ds_read_b128 v[228:231], v115 offset:32
	ds_read_b128 v[244:247], v115 offset:4640
	ds_read_b128 v[252:255], v116 offset:36928
	s_waitcnt lgkmcnt(5)
	v_mfma_f32_32x32x16_bf16 v[0:15], v[212:215], v[216:219], v[0:15]
	ds_read_b128 v[216:219], v115 offset:64
	s_waitcnt lgkmcnt(5)
	v_mfma_f32_32x32x16_bf16 v[16:31], v[212:215], v[220:223], v[16:31]
	ds_read_b128 v[212:215], v115 offset:4672
	ds_read_b128 v[220:223], v116 offset:36960
	s_waitcnt lgkmcnt(5)
	v_mfma_f32_32x32x16_bf16 v[0:15], v[224:227], v[228:231], v[0:15]
	ds_read_b128 v[228:231], v115 offset:96
	s_waitcnt lgkmcnt(5)
	v_mfma_f32_32x32x16_bf16 v[16:31], v[224:227], v[244:247], v[16:31]
	ds_read_b128 v[224:227], v115 offset:4704
	s_waitcnt lgkmcnt(4)
	v_mfma_f32_32x32x16_bf16 v[0:15], v[252:255], v[216:219], v[0:15]
	s_waitcnt lgkmcnt(3)
	v_mfma_f32_32x32x16_bf16 v[16:31], v[252:255], v[212:215], v[16:31]
	s_waitcnt lgkmcnt(1)
	v_mfma_f32_32x32x16_bf16 v[0:15], v[220:223], v[228:231], v[0:15]
	s_waitcnt lgkmcnt(0)
	v_mfma_f32_32x32x16_bf16 v[16:31], v[220:223], v[224:227], v[16:31]
	s_waitcnt vmcnt(11)
	ds_write_b128 v96, v[32:35] offset:18432
	global_load_dwordx4 v[32:35], v[86:87], off offset:128
	s_waitcnt vmcnt(11)
	ds_write_b128 v96, v[44:47] offset:23040
	global_load_dwordx4 v[44:47], v[92:93], off offset:128
	s_waitcnt vmcnt(11)
	ds_write_b128 v96, v[48:51] offset:27648
	global_load_dwordx4 v[48:51], v[94:95], off offset:128
	s_waitcnt vmcnt(11)
	ds_write_b128 v96, v[52:55] offset:32256
	global_load_dwordx4 v[52:55], v[98:99], off offset:128
	s_waitcnt vmcnt(11)
	ds_write_b128 v96, v[64:67] offset:55296
	global_load_dwordx4 v[64:67], v[84:85], off offset:128
	s_waitcnt vmcnt(11)
	ds_write_b128 v96, v[80:83] offset:59904
	global_load_dwordx4 v[76:79], v[100:101], off offset:128
	s_setprio 0
	s_waitcnt lgkmcnt(0)
	s_barrier
	s_setprio 1
	ds_read_b128 v[212:215], v116 offset:55296
	ds_read_b128 v[216:219], v115 offset:18432
	ds_read_b128 v[220:223], v115 offset:23040
	ds_read_b128 v[224:227], v116 offset:55328
	ds_read_b128 v[228:231], v115 offset:18464
	ds_read_b128 v[244:247], v115 offset:23072
	ds_read_b128 v[252:255], v116 offset:55360
	s_waitcnt lgkmcnt(5)
	v_mfma_f32_32x32x16_bf16 v[0:15], v[212:215], v[216:219], v[0:15]
	ds_read_b128 v[216:219], v115 offset:18496
	s_waitcnt lgkmcnt(5)
	v_mfma_f32_32x32x16_bf16 v[16:31], v[212:215], v[220:223], v[16:31]
	ds_read_b128 v[212:215], v115 offset:23104
	ds_read_b128 v[220:223], v116 offset:55392
	s_waitcnt lgkmcnt(5)
	v_mfma_f32_32x32x16_bf16 v[0:15], v[224:227], v[228:231], v[0:15]
	ds_read_b128 v[228:231], v115 offset:18528
	s_waitcnt lgkmcnt(5)
	v_mfma_f32_32x32x16_bf16 v[16:31], v[224:227], v[244:247], v[16:31]
	ds_read_b128 v[224:227], v115 offset:23136
	s_waitcnt lgkmcnt(4)
	v_mfma_f32_32x32x16_bf16 v[0:15], v[252:255], v[216:219], v[0:15]
	s_waitcnt lgkmcnt(3)
	v_mfma_f32_32x32x16_bf16 v[16:31], v[252:255], v[212:215], v[16:31]
	s_waitcnt lgkmcnt(1)
	v_mfma_f32_32x32x16_bf16 v[0:15], v[220:223], v[228:231], v[0:15]
	s_waitcnt lgkmcnt(0)
	v_mfma_f32_32x32x16_bf16 v[16:31], v[220:223], v[224:227], v[16:31]
	s_waitcnt vmcnt(11)
	ds_write_b128 v96, v[36:39]
	global_load_dwordx4 v[36:39], v[86:87], off offset:256
	s_waitcnt vmcnt(11)
	ds_write_b128 v96, v[40:43] offset:4608
	global_load_dwordx4 v[40:43], v[92:93], off offset:256
	s_waitcnt vmcnt(11)
	ds_write_b128 v96, v[56:59] offset:9216
	global_load_dwordx4 v[56:59], v[94:95], off offset:256
	s_waitcnt vmcnt(11)
	ds_write_b128 v96, v[60:63] offset:13824
	global_load_dwordx4 v[60:63], v[98:99], off offset:256
	s_waitcnt vmcnt(11)
	ds_write_b128 v96, v[68:71] offset:36864
	global_load_dwordx4 v[68:71], v[84:85], off offset:256
	s_waitcnt vmcnt(11)
	ds_write_b128 v96, v[72:75] offset:41472
	global_load_dwordx4 v[72:75], v[100:101], off offset:256
	s_setprio 0
	s_waitcnt lgkmcnt(0)
	s_barrier
	s_setprio 1
	ds_read_b128 v[212:215], v116 offset:36864
	ds_read_b128 v[216:219], v115
	ds_read_b128 v[220:223], v115 offset:4608
	ds_read_b128 v[224:227], v116 offset:36896
	ds_read_b128 v[228:231], v115 offset:32
	ds_read_b128 v[244:247], v115 offset:4640
	ds_read_b128 v[252:255], v116 offset:36928
	s_waitcnt lgkmcnt(5)
	v_mfma_f32_32x32x16_bf16 v[0:15], v[212:215], v[216:219], v[0:15]
	ds_read_b128 v[216:219], v115 offset:64
	s_waitcnt lgkmcnt(5)
	v_mfma_f32_32x32x16_bf16 v[16:31], v[212:215], v[220:223], v[16:31]
	ds_read_b128 v[212:215], v115 offset:4672
	ds_read_b128 v[220:223], v116 offset:36960
	s_waitcnt lgkmcnt(5)
	v_mfma_f32_32x32x16_bf16 v[0:15], v[224:227], v[228:231], v[0:15]
	ds_read_b128 v[228:231], v115 offset:96
	s_waitcnt lgkmcnt(5)
	v_mfma_f32_32x32x16_bf16 v[16:31], v[224:227], v[244:247], v[16:31]
	ds_read_b128 v[224:227], v115 offset:4704
	s_waitcnt lgkmcnt(4)
	v_mfma_f32_32x32x16_bf16 v[0:15], v[252:255], v[216:219], v[0:15]
	s_waitcnt lgkmcnt(3)
	v_mfma_f32_32x32x16_bf16 v[16:31], v[252:255], v[212:215], v[16:31]
	s_waitcnt lgkmcnt(1)
	v_mfma_f32_32x32x16_bf16 v[0:15], v[220:223], v[228:231], v[0:15]
	s_waitcnt lgkmcnt(0)
	v_mfma_f32_32x32x16_bf16 v[16:31], v[220:223], v[224:227], v[16:31]
	s_waitcnt vmcnt(11)
	ds_write_b128 v96, v[32:35] offset:18432
	global_load_dwordx4 v[32:35], v[86:87], off offset:384
	s_waitcnt vmcnt(11)
	ds_write_b128 v96, v[44:47] offset:23040
	global_load_dwordx4 v[44:47], v[92:93], off offset:384
	s_waitcnt vmcnt(11)
	ds_write_b128 v96, v[48:51] offset:27648
	global_load_dwordx4 v[48:51], v[94:95], off offset:384
	s_waitcnt vmcnt(11)
	ds_write_b128 v96, v[52:55] offset:32256
	global_load_dwordx4 v[52:55], v[98:99], off offset:384
	s_waitcnt vmcnt(11)
	ds_write_b128 v96, v[64:67] offset:55296
	global_load_dwordx4 v[64:67], v[84:85], off offset:384
	s_waitcnt vmcnt(11)
	ds_write_b128 v96, v[76:79] offset:59904
	global_load_dwordx4 v[76:79], v[100:101], off offset:384
	s_setprio 0
	s_waitcnt lgkmcnt(0)
	s_barrier
	s_setprio 1
	ds_read_b128 v[212:215], v116 offset:55296
	ds_read_b128 v[216:219], v115 offset:18432
	ds_read_b128 v[220:223], v115 offset:23040
	ds_read_b128 v[224:227], v116 offset:55328
	ds_read_b128 v[228:231], v115 offset:18464
	ds_read_b128 v[244:247], v115 offset:23072
	ds_read_b128 v[252:255], v116 offset:55360
	s_waitcnt lgkmcnt(5)
	v_mfma_f32_32x32x16_bf16 v[0:15], v[212:215], v[216:219], v[0:15]
	ds_read_b128 v[216:219], v115 offset:18496
	s_waitcnt lgkmcnt(5)
	v_mfma_f32_32x32x16_bf16 v[16:31], v[212:215], v[220:223], v[16:31]
	ds_read_b128 v[212:215], v115 offset:23104
	ds_read_b128 v[220:223], v116 offset:55392
	s_waitcnt lgkmcnt(5)
	v_mfma_f32_32x32x16_bf16 v[0:15], v[224:227], v[228:231], v[0:15]
	ds_read_b128 v[228:231], v115 offset:18528
	s_waitcnt lgkmcnt(5)
	v_mfma_f32_32x32x16_bf16 v[16:31], v[224:227], v[244:247], v[16:31]
	ds_read_b128 v[224:227], v115 offset:23136
	s_waitcnt lgkmcnt(4)
	v_mfma_f32_32x32x16_bf16 v[0:15], v[252:255], v[216:219], v[0:15]
	s_waitcnt lgkmcnt(3)
	v_mfma_f32_32x32x16_bf16 v[16:31], v[252:255], v[212:215], v[16:31]
	s_waitcnt lgkmcnt(1)
	v_mfma_f32_32x32x16_bf16 v[0:15], v[220:223], v[228:231], v[0:15]
	s_waitcnt lgkmcnt(0)
	v_mfma_f32_32x32x16_bf16 v[16:31], v[220:223], v[224:227], v[16:31]
	s_waitcnt vmcnt(11)
	ds_write_b128 v96, v[36:39]
	global_load_dwordx4 v[36:39], v[86:87], off offset:512
	s_waitcnt vmcnt(11)
	ds_write_b128 v96, v[40:43] offset:4608
	global_load_dwordx4 v[40:43], v[92:93], off offset:512
	s_waitcnt vmcnt(11)
	ds_write_b128 v96, v[56:59] offset:9216
	global_load_dwordx4 v[56:59], v[94:95], off offset:512
	s_waitcnt vmcnt(11)
	ds_write_b128 v96, v[60:63] offset:13824
	global_load_dwordx4 v[60:63], v[98:99], off offset:512
	s_waitcnt vmcnt(11)
	ds_write_b128 v96, v[68:71] offset:36864
	global_load_dwordx4 v[68:71], v[84:85], off offset:512
	s_waitcnt vmcnt(11)
	ds_write_b128 v96, v[72:75] offset:41472
	global_load_dwordx4 v[72:75], v[100:101], off offset:512
	s_setprio 0
	s_waitcnt lgkmcnt(0)
	s_barrier
	s_setprio 1
	ds_read_b128 v[212:215], v116 offset:36864
	ds_read_b128 v[216:219], v115
	ds_read_b128 v[220:223], v115 offset:4608
	ds_read_b128 v[224:227], v116 offset:36896
	ds_read_b128 v[228:231], v115 offset:32
	ds_read_b128 v[244:247], v115 offset:4640
	ds_read_b128 v[252:255], v116 offset:36928
	s_waitcnt lgkmcnt(5)
	v_mfma_f32_32x32x16_bf16 v[0:15], v[212:215], v[216:219], v[0:15]
	ds_read_b128 v[216:219], v115 offset:64
	s_waitcnt lgkmcnt(5)
	v_mfma_f32_32x32x16_bf16 v[16:31], v[212:215], v[220:223], v[16:31]
	ds_read_b128 v[212:215], v115 offset:4672
	ds_read_b128 v[220:223], v116 offset:36960
	s_waitcnt lgkmcnt(5)
	v_mfma_f32_32x32x16_bf16 v[0:15], v[224:227], v[228:231], v[0:15]
	ds_read_b128 v[228:231], v115 offset:96
	s_waitcnt lgkmcnt(5)
	v_mfma_f32_32x32x16_bf16 v[16:31], v[224:227], v[244:247], v[16:31]
	ds_read_b128 v[224:227], v115 offset:4704
	s_waitcnt lgkmcnt(4)
	v_mfma_f32_32x32x16_bf16 v[0:15], v[252:255], v[216:219], v[0:15]
	s_waitcnt lgkmcnt(3)
	v_mfma_f32_32x32x16_bf16 v[16:31], v[252:255], v[212:215], v[16:31]
	s_waitcnt lgkmcnt(1)
	v_mfma_f32_32x32x16_bf16 v[0:15], v[220:223], v[228:231], v[0:15]
	s_waitcnt lgkmcnt(0)
	v_mfma_f32_32x32x16_bf16 v[16:31], v[220:223], v[224:227], v[16:31]
	s_waitcnt vmcnt(11)
	ds_write_b128 v96, v[32:35] offset:18432
	global_load_dwordx4 v[32:35], v[86:87], off offset:640
	s_waitcnt vmcnt(11)
	ds_write_b128 v96, v[44:47] offset:23040
	global_load_dwordx4 v[44:47], v[92:93], off offset:640
	s_waitcnt vmcnt(11)
	ds_write_b128 v96, v[48:51] offset:27648
	global_load_dwordx4 v[48:51], v[94:95], off offset:640
	s_waitcnt vmcnt(11)
	ds_write_b128 v96, v[52:55] offset:32256
	global_load_dwordx4 v[52:55], v[98:99], off offset:640
	s_waitcnt vmcnt(11)
	ds_write_b128 v96, v[64:67] offset:55296
	global_load_dwordx4 v[64:67], v[84:85], off offset:640
	s_waitcnt vmcnt(11)
	ds_write_b128 v96, v[76:79] offset:59904
	global_load_dwordx4 v[76:79], v[100:101], off offset:640
	s_setprio 0
	s_waitcnt lgkmcnt(0)
	s_barrier
	s_setprio 1
	ds_read_b128 v[212:215], v116 offset:55296
	ds_read_b128 v[216:219], v115 offset:18432
	ds_read_b128 v[220:223], v115 offset:23040
	ds_read_b128 v[224:227], v116 offset:55328
	ds_read_b128 v[228:231], v115 offset:18464
	ds_read_b128 v[244:247], v115 offset:23072
	ds_read_b128 v[252:255], v116 offset:55360
	s_waitcnt lgkmcnt(5)
	v_mfma_f32_32x32x16_bf16 v[0:15], v[212:215], v[216:219], v[0:15]
	ds_read_b128 v[216:219], v115 offset:18496
	s_waitcnt lgkmcnt(5)
	v_mfma_f32_32x32x16_bf16 v[16:31], v[212:215], v[220:223], v[16:31]
	ds_read_b128 v[212:215], v115 offset:23104
	ds_read_b128 v[220:223], v116 offset:55392
	s_waitcnt lgkmcnt(5)
	v_mfma_f32_32x32x16_bf16 v[0:15], v[224:227], v[228:231], v[0:15]
	ds_read_b128 v[228:231], v115 offset:18528
	s_waitcnt lgkmcnt(5)
	v_mfma_f32_32x32x16_bf16 v[16:31], v[224:227], v[244:247], v[16:31]
	ds_read_b128 v[224:227], v115 offset:23136
	s_waitcnt lgkmcnt(4)
	v_mfma_f32_32x32x16_bf16 v[0:15], v[252:255], v[216:219], v[0:15]
	s_waitcnt lgkmcnt(3)
	v_mfma_f32_32x32x16_bf16 v[16:31], v[252:255], v[212:215], v[16:31]
	s_waitcnt lgkmcnt(1)
	v_mfma_f32_32x32x16_bf16 v[0:15], v[220:223], v[228:231], v[0:15]
	s_waitcnt lgkmcnt(0)
	v_mfma_f32_32x32x16_bf16 v[16:31], v[220:223], v[224:227], v[16:31]
	s_waitcnt vmcnt(11)
	ds_write_b128 v96, v[36:39]
	global_load_dwordx4 v[36:39], v[86:87], off offset:768
	s_waitcnt vmcnt(11)
	ds_write_b128 v96, v[40:43] offset:4608
	global_load_dwordx4 v[40:43], v[92:93], off offset:768
	s_waitcnt vmcnt(11)
	ds_write_b128 v96, v[56:59] offset:9216
	global_load_dwordx4 v[56:59], v[94:95], off offset:768
	s_waitcnt vmcnt(11)
	ds_write_b128 v96, v[60:63] offset:13824
	global_load_dwordx4 v[60:63], v[98:99], off offset:768
	s_waitcnt vmcnt(11)
	ds_write_b128 v96, v[68:71] offset:36864
	global_load_dwordx4 v[68:71], v[84:85], off offset:768
	s_waitcnt vmcnt(11)
	ds_write_b128 v96, v[72:75] offset:41472
	global_load_dwordx4 v[72:75], v[100:101], off offset:768
	s_setprio 0
	s_waitcnt lgkmcnt(0)
	s_barrier
	s_setprio 1
	ds_read_b128 v[212:215], v116 offset:36864
	ds_read_b128 v[216:219], v115
	ds_read_b128 v[220:223], v115 offset:4608
	ds_read_b128 v[224:227], v116 offset:36896
	ds_read_b128 v[228:231], v115 offset:32
	ds_read_b128 v[244:247], v115 offset:4640
	ds_read_b128 v[252:255], v116 offset:36928
	s_waitcnt lgkmcnt(5)
	v_mfma_f32_32x32x16_bf16 v[0:15], v[212:215], v[216:219], v[0:15]
	ds_read_b128 v[216:219], v115 offset:64
	s_waitcnt lgkmcnt(5)
	v_mfma_f32_32x32x16_bf16 v[16:31], v[212:215], v[220:223], v[16:31]
	ds_read_b128 v[212:215], v115 offset:4672
	ds_read_b128 v[220:223], v116 offset:36960
	s_waitcnt lgkmcnt(5)
	v_mfma_f32_32x32x16_bf16 v[0:15], v[224:227], v[228:231], v[0:15]
	ds_read_b128 v[228:231], v115 offset:96
	s_waitcnt lgkmcnt(5)
	v_mfma_f32_32x32x16_bf16 v[16:31], v[224:227], v[244:247], v[16:31]
	ds_read_b128 v[224:227], v115 offset:4704
	s_waitcnt lgkmcnt(4)
	v_mfma_f32_32x32x16_bf16 v[0:15], v[252:255], v[216:219], v[0:15]
	s_waitcnt lgkmcnt(3)
	v_mfma_f32_32x32x16_bf16 v[16:31], v[252:255], v[212:215], v[16:31]
	s_waitcnt lgkmcnt(1)
	v_mfma_f32_32x32x16_bf16 v[0:15], v[220:223], v[228:231], v[0:15]
	s_waitcnt lgkmcnt(0)
	v_mfma_f32_32x32x16_bf16 v[16:31], v[220:223], v[224:227], v[16:31]
	s_waitcnt vmcnt(11)
	ds_write_b128 v96, v[32:35] offset:18432
	global_load_dwordx4 v[32:35], v[86:87], off offset:896
	s_waitcnt vmcnt(11)
	ds_write_b128 v96, v[44:47] offset:23040
	global_load_dwordx4 v[44:47], v[92:93], off offset:896
	s_waitcnt vmcnt(11)
	ds_write_b128 v96, v[48:51] offset:27648
	global_load_dwordx4 v[48:51], v[94:95], off offset:896
	s_waitcnt vmcnt(11)
	ds_write_b128 v96, v[52:55] offset:32256
	global_load_dwordx4 v[52:55], v[98:99], off offset:896
	s_waitcnt vmcnt(11)
	ds_write_b128 v96, v[64:67] offset:55296
	global_load_dwordx4 v[64:67], v[84:85], off offset:896
	s_waitcnt vmcnt(11)
	ds_write_b128 v96, v[76:79] offset:59904
	global_load_dwordx4 v[76:79], v[100:101], off offset:896
	s_setprio 0
	s_waitcnt lgkmcnt(0)
	s_barrier
	s_setprio 1
	ds_read_b128 v[212:215], v116 offset:55296
	ds_read_b128 v[216:219], v115 offset:18432
	ds_read_b128 v[220:223], v115 offset:23040
	ds_read_b128 v[224:227], v116 offset:55328
	ds_read_b128 v[228:231], v115 offset:18464
	ds_read_b128 v[244:247], v115 offset:23072
	ds_read_b128 v[252:255], v116 offset:55360
	s_waitcnt lgkmcnt(5)
	v_mfma_f32_32x32x16_bf16 v[0:15], v[212:215], v[216:219], v[0:15]
	ds_read_b128 v[216:219], v115 offset:18496
	s_waitcnt lgkmcnt(5)
	v_mfma_f32_32x32x16_bf16 v[16:31], v[212:215], v[220:223], v[16:31]
	ds_read_b128 v[212:215], v115 offset:23104
	ds_read_b128 v[220:223], v116 offset:55392
	s_waitcnt lgkmcnt(5)
	v_mfma_f32_32x32x16_bf16 v[0:15], v[224:227], v[228:231], v[0:15]
	ds_read_b128 v[228:231], v115 offset:18528
	s_waitcnt lgkmcnt(5)
	v_mfma_f32_32x32x16_bf16 v[16:31], v[224:227], v[244:247], v[16:31]
	ds_read_b128 v[224:227], v115 offset:23136
	s_waitcnt lgkmcnt(4)
	v_mfma_f32_32x32x16_bf16 v[0:15], v[252:255], v[216:219], v[0:15]
	s_waitcnt lgkmcnt(3)
	v_mfma_f32_32x32x16_bf16 v[16:31], v[252:255], v[212:215], v[16:31]
	s_waitcnt lgkmcnt(1)
	v_mfma_f32_32x32x16_bf16 v[0:15], v[220:223], v[228:231], v[0:15]
	s_waitcnt lgkmcnt(0)
	v_mfma_f32_32x32x16_bf16 v[16:31], v[220:223], v[224:227], v[16:31]
	s_waitcnt vmcnt(11)
	ds_write_b128 v96, v[36:39]
	global_load_dwordx4 v[36:39], v[86:87], off offset:1024
	s_waitcnt vmcnt(11)
	ds_write_b128 v96, v[40:43] offset:4608
	global_load_dwordx4 v[40:43], v[92:93], off offset:1024
	s_waitcnt vmcnt(11)
	ds_write_b128 v96, v[56:59] offset:9216
	global_load_dwordx4 v[56:59], v[94:95], off offset:1024
	s_waitcnt vmcnt(11)
	ds_write_b128 v96, v[60:63] offset:13824
	global_load_dwordx4 v[60:63], v[98:99], off offset:1024
	s_waitcnt vmcnt(11)
	ds_write_b128 v96, v[68:71] offset:36864
	global_load_dwordx4 v[68:71], v[84:85], off offset:1024
	s_waitcnt vmcnt(11)
	ds_write_b128 v96, v[72:75] offset:41472
	global_load_dwordx4 v[72:75], v[100:101], off offset:1024
	s_setprio 0
	s_waitcnt lgkmcnt(0)
	s_barrier
	s_setprio 1
	ds_read_b128 v[212:215], v116 offset:36864
	ds_read_b128 v[216:219], v115
	ds_read_b128 v[220:223], v115 offset:4608
	ds_read_b128 v[224:227], v116 offset:36896
	ds_read_b128 v[228:231], v115 offset:32
	ds_read_b128 v[244:247], v115 offset:4640
	ds_read_b128 v[252:255], v116 offset:36928
	s_waitcnt lgkmcnt(5)
	v_mfma_f32_32x32x16_bf16 v[0:15], v[212:215], v[216:219], v[0:15]
	ds_read_b128 v[216:219], v115 offset:64
	s_waitcnt lgkmcnt(5)
	v_mfma_f32_32x32x16_bf16 v[16:31], v[212:215], v[220:223], v[16:31]
	ds_read_b128 v[212:215], v115 offset:4672
	ds_read_b128 v[220:223], v116 offset:36960
	s_waitcnt lgkmcnt(5)
	v_mfma_f32_32x32x16_bf16 v[0:15], v[224:227], v[228:231], v[0:15]
	ds_read_b128 v[228:231], v115 offset:96
	s_waitcnt lgkmcnt(5)
	v_mfma_f32_32x32x16_bf16 v[16:31], v[224:227], v[244:247], v[16:31]
	ds_read_b128 v[224:227], v115 offset:4704
	s_waitcnt lgkmcnt(4)
	v_mfma_f32_32x32x16_bf16 v[0:15], v[252:255], v[216:219], v[0:15]
	s_waitcnt lgkmcnt(3)
	v_mfma_f32_32x32x16_bf16 v[16:31], v[252:255], v[212:215], v[16:31]
	s_waitcnt lgkmcnt(1)
	v_mfma_f32_32x32x16_bf16 v[0:15], v[220:223], v[228:231], v[0:15]
	s_waitcnt lgkmcnt(0)
	v_mfma_f32_32x32x16_bf16 v[16:31], v[220:223], v[224:227], v[16:31]
	s_waitcnt vmcnt(11)
	ds_write_b128 v96, v[32:35] offset:18432
	global_load_dwordx4 v[32:35], v[86:87], off offset:1152
	s_waitcnt vmcnt(11)
	ds_write_b128 v96, v[44:47] offset:23040
	global_load_dwordx4 v[44:47], v[92:93], off offset:1152
	s_waitcnt vmcnt(11)
	ds_write_b128 v96, v[48:51] offset:27648
	global_load_dwordx4 v[48:51], v[94:95], off offset:1152
	s_waitcnt vmcnt(11)
	ds_write_b128 v96, v[52:55] offset:32256
	global_load_dwordx4 v[52:55], v[98:99], off offset:1152
	s_waitcnt vmcnt(11)
	ds_write_b128 v96, v[64:67] offset:55296
	global_load_dwordx4 v[64:67], v[84:85], off offset:1152
	s_waitcnt vmcnt(11)
	ds_write_b128 v96, v[76:79] offset:59904
	global_load_dwordx4 v[76:79], v[100:101], off offset:1152
	s_setprio 0
	s_waitcnt lgkmcnt(0)
	s_barrier
	s_setprio 1
	ds_read_b128 v[212:215], v116 offset:55296
	ds_read_b128 v[216:219], v115 offset:18432
	ds_read_b128 v[220:223], v115 offset:23040
	ds_read_b128 v[224:227], v116 offset:55328
	ds_read_b128 v[228:231], v115 offset:18464
	ds_read_b128 v[244:247], v115 offset:23072
	ds_read_b128 v[252:255], v116 offset:55360
	s_waitcnt lgkmcnt(5)
	v_mfma_f32_32x32x16_bf16 v[0:15], v[212:215], v[216:219], v[0:15]
	ds_read_b128 v[216:219], v115 offset:18496
	s_waitcnt lgkmcnt(5)
	v_mfma_f32_32x32x16_bf16 v[16:31], v[212:215], v[220:223], v[16:31]
	ds_read_b128 v[212:215], v115 offset:23104
	ds_read_b128 v[220:223], v116 offset:55392
	s_waitcnt lgkmcnt(5)
	v_mfma_f32_32x32x16_bf16 v[0:15], v[224:227], v[228:231], v[0:15]
	ds_read_b128 v[228:231], v115 offset:18528
	s_waitcnt lgkmcnt(5)
	v_mfma_f32_32x32x16_bf16 v[16:31], v[224:227], v[244:247], v[16:31]
	ds_read_b128 v[224:227], v115 offset:23136
	s_waitcnt lgkmcnt(4)
	v_mfma_f32_32x32x16_bf16 v[0:15], v[252:255], v[216:219], v[0:15]
	s_waitcnt lgkmcnt(3)
	v_mfma_f32_32x32x16_bf16 v[16:31], v[252:255], v[212:215], v[16:31]
	s_waitcnt lgkmcnt(1)
	v_mfma_f32_32x32x16_bf16 v[0:15], v[220:223], v[228:231], v[0:15]
	s_waitcnt lgkmcnt(0)
	v_mfma_f32_32x32x16_bf16 v[16:31], v[220:223], v[224:227], v[16:31]
	s_waitcnt vmcnt(11)
	ds_write_b128 v96, v[36:39]
	global_load_dwordx4 v[36:39], v[86:87], off offset:1280
	s_waitcnt vmcnt(11)
	ds_write_b128 v96, v[40:43] offset:4608
	global_load_dwordx4 v[40:43], v[92:93], off offset:1280
	s_waitcnt vmcnt(11)
	ds_write_b128 v96, v[56:59] offset:9216
	global_load_dwordx4 v[56:59], v[94:95], off offset:1280
	s_waitcnt vmcnt(11)
	ds_write_b128 v96, v[60:63] offset:13824
	global_load_dwordx4 v[60:63], v[98:99], off offset:1280
	s_waitcnt vmcnt(11)
	ds_write_b128 v96, v[68:71] offset:36864
	global_load_dwordx4 v[68:71], v[84:85], off offset:1280
	s_waitcnt vmcnt(11)
	ds_write_b128 v96, v[72:75] offset:41472
	global_load_dwordx4 v[72:75], v[100:101], off offset:1280
	s_setprio 0
	s_waitcnt lgkmcnt(0)
	s_barrier
	s_setprio 1
	ds_read_b128 v[212:215], v116 offset:36864
	ds_read_b128 v[216:219], v115
	ds_read_b128 v[220:223], v115 offset:4608
	ds_read_b128 v[224:227], v116 offset:36896
	ds_read_b128 v[228:231], v115 offset:32
	ds_read_b128 v[244:247], v115 offset:4640
	ds_read_b128 v[252:255], v116 offset:36928
	s_waitcnt lgkmcnt(5)
	v_mfma_f32_32x32x16_bf16 v[0:15], v[212:215], v[216:219], v[0:15]
	ds_read_b128 v[216:219], v115 offset:64
	s_waitcnt lgkmcnt(5)
	v_mfma_f32_32x32x16_bf16 v[16:31], v[212:215], v[220:223], v[16:31]
	ds_read_b128 v[212:215], v115 offset:4672
	ds_read_b128 v[220:223], v116 offset:36960
	s_waitcnt lgkmcnt(5)
	v_mfma_f32_32x32x16_bf16 v[0:15], v[224:227], v[228:231], v[0:15]
	ds_read_b128 v[228:231], v115 offset:96
	s_waitcnt lgkmcnt(5)
	v_mfma_f32_32x32x16_bf16 v[16:31], v[224:227], v[244:247], v[16:31]
	ds_read_b128 v[224:227], v115 offset:4704
	s_waitcnt lgkmcnt(4)
	v_mfma_f32_32x32x16_bf16 v[0:15], v[252:255], v[216:219], v[0:15]
	s_waitcnt lgkmcnt(3)
	v_mfma_f32_32x32x16_bf16 v[16:31], v[252:255], v[212:215], v[16:31]
	s_waitcnt lgkmcnt(1)
	v_mfma_f32_32x32x16_bf16 v[0:15], v[220:223], v[228:231], v[0:15]
	s_waitcnt lgkmcnt(0)
	v_mfma_f32_32x32x16_bf16 v[16:31], v[220:223], v[224:227], v[16:31]
	s_waitcnt vmcnt(11)
	ds_write_b128 v96, v[32:35] offset:18432
	global_load_dwordx4 v[32:35], v[86:87], off offset:1408
	s_waitcnt vmcnt(11)
	ds_write_b128 v96, v[44:47] offset:23040
	global_load_dwordx4 v[44:47], v[92:93], off offset:1408
	s_waitcnt vmcnt(11)
	ds_write_b128 v96, v[48:51] offset:27648
	global_load_dwordx4 v[48:51], v[94:95], off offset:1408
	s_waitcnt vmcnt(11)
	ds_write_b128 v96, v[52:55] offset:32256
	global_load_dwordx4 v[52:55], v[98:99], off offset:1408
	s_waitcnt vmcnt(11)
	ds_write_b128 v96, v[64:67] offset:55296
	global_load_dwordx4 v[64:67], v[84:85], off offset:1408
	s_waitcnt vmcnt(11)
	ds_write_b128 v96, v[76:79] offset:59904
	global_load_dwordx4 v[76:79], v[100:101], off offset:1408
	s_setprio 0
	s_waitcnt lgkmcnt(0)
	s_barrier
	s_setprio 1
	ds_read_b128 v[212:215], v116 offset:55296
	ds_read_b128 v[216:219], v115 offset:18432
	ds_read_b128 v[220:223], v115 offset:23040
	ds_read_b128 v[224:227], v116 offset:55328
	ds_read_b128 v[228:231], v115 offset:18464
	ds_read_b128 v[244:247], v115 offset:23072
	ds_read_b128 v[252:255], v116 offset:55360
	s_waitcnt lgkmcnt(5)
	v_mfma_f32_32x32x16_bf16 v[0:15], v[212:215], v[216:219], v[0:15]
	ds_read_b128 v[216:219], v115 offset:18496
	s_waitcnt lgkmcnt(5)
	v_mfma_f32_32x32x16_bf16 v[16:31], v[212:215], v[220:223], v[16:31]
	ds_read_b128 v[212:215], v115 offset:23104
	ds_read_b128 v[220:223], v116 offset:55392
	s_waitcnt lgkmcnt(5)
	v_mfma_f32_32x32x16_bf16 v[0:15], v[224:227], v[228:231], v[0:15]
	ds_read_b128 v[228:231], v115 offset:18528
	s_waitcnt lgkmcnt(5)
	v_mfma_f32_32x32x16_bf16 v[16:31], v[224:227], v[244:247], v[16:31]
	ds_read_b128 v[224:227], v115 offset:23136
	s_waitcnt lgkmcnt(4)
	v_mfma_f32_32x32x16_bf16 v[0:15], v[252:255], v[216:219], v[0:15]
	s_waitcnt lgkmcnt(3)
	v_mfma_f32_32x32x16_bf16 v[16:31], v[252:255], v[212:215], v[16:31]
	s_waitcnt lgkmcnt(1)
	v_mfma_f32_32x32x16_bf16 v[0:15], v[220:223], v[228:231], v[0:15]
	s_waitcnt lgkmcnt(0)
	v_mfma_f32_32x32x16_bf16 v[16:31], v[220:223], v[224:227], v[16:31]
	s_waitcnt vmcnt(11)
	ds_write_b128 v96, v[36:39]
	s_waitcnt vmcnt(10)
	ds_write_b128 v96, v[40:43] offset:4608
	s_waitcnt vmcnt(9)
	ds_write_b128 v96, v[56:59] offset:9216
	s_waitcnt vmcnt(8)
	ds_write_b128 v96, v[60:63] offset:13824
	s_waitcnt vmcnt(7)
	ds_write_b128 v96, v[68:71] offset:36864
	s_waitcnt vmcnt(6)
	ds_write_b128 v96, v[72:75] offset:41472
	s_setprio 0
	s_waitcnt lgkmcnt(0)
	s_barrier
	s_setprio 1
	ds_read_b128 v[212:215], v116 offset:36864
	ds_read_b128 v[216:219], v115
	ds_read_b128 v[220:223], v115 offset:4608
	ds_read_b128 v[224:227], v116 offset:36896
	ds_read_b128 v[228:231], v115 offset:32
	ds_read_b128 v[244:247], v115 offset:4640
	ds_read_b128 v[252:255], v116 offset:36928
	s_waitcnt lgkmcnt(5)
	v_mfma_f32_32x32x16_bf16 v[0:15], v[212:215], v[216:219], v[0:15]
	ds_read_b128 v[216:219], v115 offset:64
	s_waitcnt lgkmcnt(5)
	v_mfma_f32_32x32x16_bf16 v[16:31], v[212:215], v[220:223], v[16:31]
	ds_read_b128 v[212:215], v115 offset:4672
	ds_read_b128 v[220:223], v116 offset:36960
	s_waitcnt lgkmcnt(5)
	v_mfma_f32_32x32x16_bf16 v[0:15], v[224:227], v[228:231], v[0:15]
	ds_read_b128 v[228:231], v115 offset:96
	s_waitcnt lgkmcnt(5)
	v_mfma_f32_32x32x16_bf16 v[16:31], v[224:227], v[244:247], v[16:31]
	ds_read_b128 v[224:227], v115 offset:4704
	s_waitcnt lgkmcnt(4)
	v_mfma_f32_32x32x16_bf16 v[0:15], v[252:255], v[216:219], v[0:15]
	s_waitcnt lgkmcnt(3)
	v_mfma_f32_32x32x16_bf16 v[16:31], v[252:255], v[212:215], v[16:31]
	s_waitcnt lgkmcnt(1)
	v_mfma_f32_32x32x16_bf16 v[0:15], v[220:223], v[228:231], v[0:15]
	s_waitcnt lgkmcnt(0)
	v_mfma_f32_32x32x16_bf16 v[16:31], v[220:223], v[224:227], v[16:31]
	s_waitcnt vmcnt(5)
	ds_write_b128 v96, v[32:35] offset:18432
	s_waitcnt vmcnt(4)
	ds_write_b128 v96, v[44:47] offset:23040
	s_waitcnt vmcnt(3)
	ds_write_b128 v96, v[48:51] offset:27648
	s_waitcnt vmcnt(2)
	ds_write_b128 v96, v[52:55] offset:32256
	s_waitcnt vmcnt(1)
	ds_write_b128 v96, v[64:67] offset:55296
	s_waitcnt vmcnt(0)
	ds_write_b128 v96, v[76:79] offset:59904
	s_setprio 0
	s_waitcnt lgkmcnt(0)
	s_barrier
	s_setprio 1
	ds_read_b128 v[212:215], v116 offset:55296
	ds_read_b128 v[216:219], v115 offset:18432
	ds_read_b128 v[220:223], v115 offset:23040
	ds_read_b128 v[224:227], v116 offset:55328
	ds_read_b128 v[228:231], v115 offset:18464
	ds_read_b128 v[244:247], v115 offset:23072
	ds_read_b128 v[252:255], v116 offset:55360
	s_waitcnt lgkmcnt(5)
	v_mfma_f32_32x32x16_bf16 v[0:15], v[212:215], v[216:219], v[0:15]
	ds_read_b128 v[216:219], v115 offset:18496
	s_waitcnt lgkmcnt(5)
	v_mfma_f32_32x32x16_bf16 v[16:31], v[212:215], v[220:223], v[16:31]
	ds_read_b128 v[212:215], v115 offset:23104
	ds_read_b128 v[220:223], v116 offset:55392
	s_waitcnt lgkmcnt(5)
	v_mfma_f32_32x32x16_bf16 v[0:15], v[224:227], v[228:231], v[0:15]
	ds_read_b128 v[228:231], v115 offset:18528
	s_waitcnt lgkmcnt(5)
	v_mfma_f32_32x32x16_bf16 v[16:31], v[224:227], v[244:247], v[16:31]
	ds_read_b128 v[224:227], v115 offset:23136
	s_waitcnt lgkmcnt(4)
	v_mfma_f32_32x32x16_bf16 v[0:15], v[252:255], v[216:219], v[0:15]
	s_waitcnt lgkmcnt(3)
	v_mfma_f32_32x32x16_bf16 v[16:31], v[252:255], v[212:215], v[16:31]
	s_waitcnt lgkmcnt(1)
	v_mfma_f32_32x32x16_bf16 v[0:15], v[220:223], v[228:231], v[0:15]
	s_waitcnt lgkmcnt(0)
	v_mfma_f32_32x32x16_bf16 v[16:31], v[220:223], v[224:227], v[16:31]
	s_setprio 0
	s_lshl_b32 s3, s3, 7
	s_min_i32 s6, s3, 0x4000
	s_ashr_i32 s6, s6, 11
	s_mul_hi_i32 s7, s6, 0x9000
	s_mul_i32 s6, s6, 0x9000
	v_lshl_or_b32 v32, s4, 6, v114
	s_add_u32 s6, s0, s6
	v_add_u32_e32 v34, s3, v169
	v_ashrrev_i32_e32 v33, 31, v32
	s_addc_u32 s7, s1, s7
	v_lshlrev_b64 v[32:33], 2, v[32:33]
	v_ashrrev_i32_e32 v35, 31, v34
	v_lshl_add_u64 v[36:37], s[6:7], 0, v[32:33]
	v_lshl_add_u64 v[38:39], s[92:93], 0, v[32:33]
	v_lshlrev_b64 v[32:33], 12, v[34:35]
	v_or_b32_e32 v34, 32, v34
	v_ashrrev_i32_e32 v35, 31, v34
	v_lshlrev_b64 v[34:35], 12, v[34:35]
	s_barrier
	v_lshl_add_u64 v[32:33], v[38:39], 0, v[32:33]
	v_lshl_add_u64 v[34:35], v[38:39], 0, v[34:35]
	global_load_dwordx4 v[38:41], v[36:37], off
	global_load_dwordx4 v[42:45], v[32:33], off
	global_load_dwordx4 v[46:49], v[34:35], off
	s_add_i32 s2, s2, s94
	s_cmp_lt_i32 s2, s26
	s_waitcnt vmcnt(2)
	v_pk_mul_f32 v[38:39], v[38:39], 0.5 op_sel_hi:[1,0]
	s_waitcnt vmcnt(1)
	v_pk_fma_f32 v[0:1], v[0:1], v[38:39], v[42:43]
	s_waitcnt vmcnt(0)
	v_pk_fma_f32 v[16:17], v[16:17], v[38:39], v[46:47]
	v_pk_mul_f32 v[38:39], v[40:41], 0.5 op_sel_hi:[1,0]
	v_pk_fma_f32 v[2:3], v[2:3], v[38:39], v[44:45]
	global_store_dwordx4 v[32:33], v[0:3], off
	v_pk_fma_f32 v[18:19], v[18:19], v[38:39], v[48:49]
	global_load_dwordx4 v[0:3], v[36:37], off offset:32
	global_load_dwordx4 v[38:41], v[34:35], off offset:32
	s_waitcnt vmcnt(1)
	v_pk_mul_f32 v[42:43], v[0:1], 0.5 op_sel_hi:[1,0]
	global_store_dwordx4 v[34:35], v[16:19], off
	global_load_dwordx4 v[16:19], v[32:33], off offset:32
	s_waitcnt vmcnt(0)
	v_pk_fma_f32 v[0:1], v[4:5], v[42:43], v[16:17]
	v_pk_mul_f32 v[16:17], v[2:3], 0.5 op_sel_hi:[1,0]
	v_pk_fma_f32 v[4:5], v[20:21], v[42:43], v[38:39]
	v_pk_fma_f32 v[2:3], v[6:7], v[16:17], v[18:19]
	global_store_dwordx4 v[32:33], v[0:3], off offset:32
	v_pk_fma_f32 v[6:7], v[22:23], v[16:17], v[40:41]
	global_load_dwordx4 v[0:3], v[36:37], off offset:64
	global_load_dwordx4 v[16:19], v[34:35], off offset:64
	s_waitcnt vmcnt(1)
	v_pk_mul_f32 v[20:21], v[0:1], 0.5 op_sel_hi:[1,0]
	global_store_dwordx4 v[34:35], v[4:7], off offset:32
	global_load_dwordx4 v[4:7], v[32:33], off offset:64
	s_waitcnt vmcnt(0)
	v_pk_fma_f32 v[0:1], v[8:9], v[20:21], v[4:5]
	v_pk_mul_f32 v[8:9], v[2:3], 0.5 op_sel_hi:[1,0]
	v_pk_fma_f32 v[4:5], v[24:25], v[20:21], v[16:17]
	v_pk_fma_f32 v[2:3], v[10:11], v[8:9], v[6:7]
	global_store_dwordx4 v[32:33], v[0:3], off offset:64
	v_pk_fma_f32 v[6:7], v[26:27], v[8:9], v[18:19]
	global_load_dwordx4 v[0:3], v[36:37], off offset:96
	global_load_dwordx4 v[8:11], v[34:35], off offset:96
	s_waitcnt vmcnt(1)
	v_pk_mul_f32 v[16:17], v[0:1], 0.5 op_sel_hi:[1,0]
	global_store_dwordx4 v[34:35], v[4:7], off offset:64
	global_load_dwordx4 v[4:7], v[32:33], off offset:96
	s_waitcnt vmcnt(0)
	v_pk_fma_f32 v[0:1], v[12:13], v[16:17], v[4:5]
	v_pk_fma_f32 v[4:5], v[28:29], v[16:17], v[8:9]
	v_pk_mul_f32 v[8:9], v[2:3], 0.5 op_sel_hi:[1,0]
	v_pk_fma_f32 v[2:3], v[14:15], v[8:9], v[6:7]
	v_pk_fma_f32 v[6:7], v[30:31], v[8:9], v[10:11]
	global_store_dwordx4 v[32:33], v[0:3], off offset:96
	global_store_dwordx4 v[34:35], v[4:7], off offset:96
	s_cbranch_scc1 .LBB0_338
	s_mov_b32 s24, s69

.LBB0_390:
	v_min_i32_e32 v0, 0x4000, v12
	v_ashrrev_i32_e32 v0, 11, v0
	v_mul_hi_i32_i24_e32 v1, 0x9000, v0
	v_mul_i32_i24_e32 v0, 0x9000, v0
	v_lshl_add_u64 v[0:1], s[2:3], 0, v[0:1]
	v_lshl_add_u64 v[26:27], v[0:1], 0, s[10:11]
	v_lshl_add_u64 v[58:59], s[92:93], 0, v[20:21]
	v_lshl_add_u64 v[4:5], v[26:27], 0, v[96:97]
	v_lshl_add_u64 v[24:25], v[0:1], 0, v[96:97]
	global_load_dwordx4 v[38:41], v[58:59], off offset:16
	global_load_dwordx4 v[8:11], v[58:59], off
	global_load_dwordx4 v[42:45], v[16:17], off offset:16
	global_load_dwordx4 v[46:49], v[16:17], off
	global_load_dwordx4 v[50:53], v[24:25], off offset:16
	global_load_dwordx4 v[54:57], v[24:25], off
	global_load_dwordx4 v[0:3], v[4:5], off offset:16
	global_load_dwordx4 v[4:7], v[4:5], off
	v_mov_b32_e32 v23, v97
	v_lshl_add_u64 v[26:27], v[26:27], 0, v[22:23]
	v_lshl_add_u64 v[30:31], s[92:93], 0, v[18:19]
	v_add_u32_e32 v12, s8, v12
	v_lshl_add_u64 v[18:19], v[18:19], 0, s[30:31]
	v_lshl_add_u64 v[20:21], v[20:21], 0, s[14:15]
	s_waitcnt vmcnt(7)
	v_mov_b32_e32 v67, v39
	s_waitcnt vmcnt(6)
	v_mov_b32_e32 v66, v9
	v_pk_mul_f32 v[66:67], v[66:67], v[66:67]
	s_waitcnt vmcnt(1)
	v_pk_add_f32 v[60:61], v[0:1], 1.0 op_sel_hi:[1,0]
	s_waitcnt vmcnt(0)
	v_pk_add_f32 v[62:63], v[6:7], 1.0 op_sel_hi:[1,0]
	v_mov_b32_e32 v6, v8
	v_mov_b32_e32 v7, v38
	v_mov_b32_e32 v0, v10
	v_mov_b32_e32 v1, v40
	v_pk_fma_f32 v[6:7], v[6:7], v[6:7], v[66:67]
	v_pk_add_f32 v[64:65], v[4:5], 1.0 op_sel_hi:[1,0]
	v_mov_b32_e32 v4, v11
	v_mov_b32_e32 v5, v41
	v_pk_fma_f32 v[0:1], v[0:1], v[0:1], v[6:7]
	v_pk_add_f32 v[68:69], v[2:3], 1.0 op_sel_hi:[1,0]
	v_pk_fma_f32 v[66:67], v[4:5], v[4:5], v[0:1]
	global_load_dwordx4 v[0:3], v[58:59], off offset:2064
	global_load_dwordx4 v[4:7], v[58:59], off offset:2048
	global_load_dwordx4 v[86:89], v[14:15], off offset:16
	global_load_dwordx4 v[90:93], v[14:15], off
	global_load_dwordx4 v[98:101], v[24:25], off offset:2064
	global_load_dwordx4 v[106:109], v[24:25], off offset:2048
	global_load_dwordx4 v[110:113], v[26:27], off offset:16
	global_load_dwordx4 v[114:117], v[26:27], off
	v_add_f32_e32 v13, v66, v67
	s_waitcnt vmcnt(7)
	v_mov_b32_e32 v75, v1
	s_waitcnt vmcnt(6)
	v_mov_b32_e32 v74, v5
	v_mov_b32_e32 v72, v4
	v_mov_b32_e32 v73, v0
	v_pk_mul_f32 v[74:75], v[74:75], v[74:75]
	v_mov_b32_e32 v58, v6
	v_mov_b32_e32 v59, v2
	v_pk_fma_f32 v[72:73], v[72:73], v[72:73], v[74:75]
	v_mov_b32_e32 v70, v7
	v_mov_b32_e32 v71, v3
	v_pk_fma_f32 v[58:59], v[58:59], v[58:59], v[72:73]
	v_pk_fma_f32 v[58:59], v[70:71], v[70:71], v[58:59]
	v_add_f32_e32 v13, v13, v58
	v_add_f32_e32 v13, v13, v59
	v_mov_b32_e32 v23, v13
	v_mov_b32_e32 v255, v13
	s_nop 1
	v_permlane32_swap_b32_e32 v23, v255
	s_waitcnt lgkmcnt(0)
	v_add_f32_e32 v13, v23, v255
	v_mov_b32_e32 v23, v13
	v_mov_b32_e32 v255, v13
	s_nop 1
	v_permlane16_swap_b32_e32 v23, v255
	s_nop 1
	v_mov_b32_dpp v23, v255 quad_perm:[0,1,2,3] row_mask:0x5 bank_mask:0xf
	s_nop 0
	v_add_f32_e32 v13, v13, v23
	s_nop 1
	v_mov_b32_dpp v23, v13 row_ror:8 row_mask:0xf bank_mask:0xf
	s_nop 0
	v_add_f32_e32 v13, v13, v23
	s_nop 1
	v_mov_b32_dpp v23, v13 row_shl:4 row_mask:0xf bank_mask:0x5
	v_mov_b32_dpp v23, v13 row_shr:4 row_mask:0xf bank_mask:0xa
	s_nop 0
	v_add_f32_e32 v13, v13, v23
	s_nop 1
	v_mov_b32_dpp v23, v13 quad_perm:[2,3,0,1] row_mask:0xf bank_mask:0xf
	v_add_f32_e32 v13, v13, v23
	s_nop 1
	v_add_f32_dpp v13, v13, v13 quad_perm:[1,0,3,2] row_mask:0xf bank_mask:0xf
	v_fmamk_f32 v13, v13, 0x3a800000, v163
	v_cmp_gt_f32_e32 vcc, s86, v13
	v_mul_f32_e32 v23, 0x4b800000, v13
	s_nop 0
	v_cndmask_b32_e32 v13, v13, v23, vcc
	v_rsq_f32_e32 v13, v13
	s_nop 0
	v_mul_f32_e32 v23, 0x45800000, v13
	v_cndmask_b32_e32 v28, v13, v23, vcc
	v_pk_mul_f32 v[8:9], v[8:9], v[28:29] op_sel_hi:[1,0]
	v_pk_mul_f32 v[10:11], v[10:11], v[28:29] op_sel_hi:[1,0]
	v_pk_mul_f32 v[8:9], v[46:47], v[8:9]
	v_pk_mul_f32 v[10:11], v[48:49], v[10:11]
	v_pk_fma_f32 v[8:9], v[64:65], v[8:9], v[54:55]
	v_pk_fma_f32 v[10:11], v[62:63], v[10:11], v[56:57]
	v_cvt_pk_bf16_f32 v8, v8, v9
	v_cvt_pk_bf16_f32 v9, v10, v11
	v_pk_mul_f32 v[10:11], v[38:39], v[28:29] op_sel_hi:[1,0]
	v_pk_mul_f32 v[38:39], v[40:41], v[28:29] op_sel_hi:[1,0]
	v_pk_mul_f32 v[10:11], v[10:11], v[42:43]
	v_pk_mul_f32 v[38:39], v[38:39], v[44:45]
	v_pk_fma_f32 v[10:11], v[10:11], v[60:61], v[50:51]
	v_pk_fma_f32 v[38:39], v[38:39], v[68:69], v[52:53]
	v_add_co_u32_e32 v30, vcc, s28, v30
	v_cvt_pk_bf16_f32 v10, v10, v11
	v_cvt_pk_bf16_f32 v11, v38, v39
	v_addc_co_u32_e32 v31, vcc, 0, v31, vcc
	global_store_dwordx4 v[30:31], v[8:11], off
	v_pk_mul_f32 v[4:5], v[4:5], v[28:29] op_sel_hi:[1,0]
	v_pk_mul_f32 v[6:7], v[6:7], v[28:29] op_sel_hi:[1,0]
	v_pk_mul_f32 v[0:1], v[0:1], v[28:29] op_sel_hi:[1,0]
	v_pk_mul_f32 v[2:3], v[2:3], v[28:29] op_sel_hi:[1,0]
	v_cmp_lt_i32_e32 vcc, s29, v12
	s_or_b64 s[6:7], vcc, s[6:7]
	s_waitcnt vmcnt(6)
	v_pk_mul_f32 v[0:1], v[0:1], v[86:87]
	s_waitcnt vmcnt(5)
	v_pk_mul_f32 v[4:5], v[4:5], v[90:91]
	v_pk_mul_f32 v[6:7], v[6:7], v[92:93]
	v_pk_mul_f32 v[2:3], v[2:3], v[88:89]
	s_waitcnt vmcnt(1)
	v_pk_add_f32 v[24:25], v[114:115], 1.0 op_sel_hi:[1,0]
	v_pk_fma_f32 v[4:5], v[4:5], v[24:25], v[106:107]
	v_pk_add_f32 v[24:25], v[116:117], 1.0 op_sel_hi:[1,0]
	v_cvt_pk_bf16_f32 v4, v4, v5
	v_pk_fma_f32 v[6:7], v[6:7], v[24:25], v[108:109]
	v_cvt_pk_bf16_f32 v5, v6, v7
	v_pk_add_f32 v[6:7], v[110:111], 1.0 op_sel_hi:[1,0]
	v_pk_fma_f32 v[0:1], v[0:1], v[6:7], v[98:99]
	v_pk_add_f32 v[6:7], v[112:113], 1.0 op_sel_hi:[1,0]
	v_pk_fma_f32 v[2:3], v[2:3], v[6:7], v[100:101]
	v_cvt_pk_bf16_f32 v6, v0, v1
	v_cvt_pk_bf16_f32 v7, v2, v3
	global_store_dwordx4 v[30:31], v[4:7], off offset:1024
	s_andn2_b64 exec, exec, s[6:7]
	s_cbranch_execnz .LBB0_390

.LBB0_472:
	s_ashr_i32 s47, s46, 31
	s_lshl_b64 s[40:41], s[46:47], 18
	s_add_u32 s3, s82, s40
	s_addc_u32 s7, s83, s41
	s_and_b64 s[40:41], s[12:13], exec
	s_cselect_b32 s41, s7, 0
	s_cselect_b32 s40, s3, 0
	s_ashr_i32 s45, s44, 31
	s_lshl_b64 s[42:43], s[44:45], 18
	v_readlane_b32 s14, v251, 56
	v_readlane_b32 s15, v251, 57
	s_add_u32 s3, s14, s42
	s_addc_u32 s7, s15, s43
	s_and_b64 s[42:43], s[12:13], exec
	s_cselect_b32 s43, s7, 0
	s_cselect_b32 s42, s3, 0
	v_lshl_add_u64 v[4:5], s[40:41], 0, v[0:1]
	v_lshl_add_u64 v[0:1], s[42:43], 0, v[0:1]
	v_lshl_add_u64 v[146:147], v[0:1], 0, v[96:97]
	v_lshrrev_b32_e32 v0, 1, v2
	v_and_b32_e32 v1, 31, v2
	v_and_or_b32 v1, v0, s81, v1
	v_lshrrev_b32_e32 v0, 2, v2
	v_and_b32_e32 v0, 8, v0
	v_lshl_add_u64 v[148:149], v[4:5], 0, v[96:97]
	v_mad_u64_u32 v[4:5], s[40:41], v1, s84, v[0:1]
	v_and_b32_e32 v1, 0x5f, v2
	v_mad_u32_u24 v0, v1, s84, v0
	v_lshl_add_u32 v178, v4, 1, 0
	v_lshl_add_u32 v96, v0, 1, 0
	v_add_u32_e32 v179, 0xd800, v177
	s_setprio 1
	ds_read_b128 v[212:215], v96 offset:36864
	ds_read_b128 v[216:219], v178
	ds_read_b128 v[220:223], v178 offset:4608
	ds_read_b128 v[224:227], v96 offset:36896
	ds_read_b128 v[228:231], v178 offset:32
	ds_read_b128 v[244:247], v178 offset:4640
	ds_read_b128 v[252:255], v96 offset:41472
	s_waitcnt lgkmcnt(5)
	v_mfma_f32_32x32x16_bf16 v[48:63], v[212:215], v[216:219], 0
	s_waitcnt lgkmcnt(4)
	v_mfma_f32_32x32x16_bf16 v[32:47], v[212:215], v[220:223], 0
	ds_read_b128 v[212:215], v96 offset:41504
	s_waitcnt lgkmcnt(3)
	v_mfma_f32_32x32x16_bf16 v[48:63], v[224:227], v[228:231], v[48:63]
	s_waitcnt lgkmcnt(2)
	v_mfma_f32_32x32x16_bf16 v[32:47], v[224:227], v[244:247], v[32:47]
	ds_read_b128 v[224:227], v96 offset:36928
	s_waitcnt lgkmcnt(2)
	v_mfma_f32_32x32x16_bf16 v[16:31], v[252:255], v[216:219], 0
	ds_read_b128 v[216:219], v178 offset:64
	v_mfma_f32_32x32x16_bf16 v[0:15], v[252:255], v[220:223], 0
	ds_read_b128 v[252:255], v178 offset:4672
	ds_read_b128 v[220:223], v96 offset:41536
	s_waitcnt lgkmcnt(4)
	v_mfma_f32_32x32x16_bf16 v[16:31], v[212:215], v[228:231], v[16:31]
	ds_read_b128 v[228:231], v96 offset:36960
	v_mfma_f32_32x32x16_bf16 v[0:15], v[212:215], v[244:247], v[0:15]
	ds_read_b128 v[212:215], v178 offset:96
	ds_read_b128 v[244:247], v178 offset:4704
	s_waitcnt lgkmcnt(5)
	v_mfma_f32_32x32x16_bf16 v[48:63], v[224:227], v[216:219], v[48:63]
	s_mov_b32 s3, 0x10000
	v_add_co_u32_e32 v154, vcc, s3, v152
	s_mov_b32 s7, 0x20000
	s_nop 0
	v_addc_co_u32_e32 v155, vcc, 0, v153, vcc
	v_add_co_u32_e32 v156, vcc, s7, v152
	s_mov_b32 s8, 0x30000
	s_nop 0
	s_waitcnt lgkmcnt(4)
	v_mfma_f32_32x32x16_bf16 v[32:47], v[224:227], v[252:255], v[32:47]
	ds_read_b128 v[224:227], v96 offset:41568
	v_addc_co_u32_e32 v157, vcc, 0, v153, vcc
	v_add_co_u32_e32 v158, vcc, s8, v152
	s_waitcnt vmcnt(7)
	ds_write_b128 v177, v[100:103] offset:18432
	s_waitcnt vmcnt(6)
	ds_write_b128 v177, v[104:107] offset:23040
	s_waitcnt lgkmcnt(6)
	v_mfma_f32_32x32x16_bf16 v[16:31], v[220:223], v[216:219], v[16:31]
	s_waitcnt vmcnt(5)
	ds_write_b128 v177, v[108:111] offset:27648
	s_waitcnt vmcnt(4)
	ds_write_b128 v177, v[112:115] offset:32256
	v_mfma_f32_32x32x16_bf16 v[0:15], v[220:223], v[252:255], v[0:15]
	s_waitcnt vmcnt(3)
	ds_write_b128 v177, v[116:119] offset:55296
	s_waitcnt vmcnt(2)
	ds_write_b128 v177, v[120:123] offset:59904
	s_waitcnt vmcnt(1)
	ds_write_b128 v177, v[128:131] offset:64512
	s_waitcnt lgkmcnt(9)
	v_mfma_f32_32x32x16_bf16 v[48:63], v[228:231], v[212:215], v[48:63]
	s_waitcnt vmcnt(0)
	ds_write_b128 v179, v[124:127] offset:13824
	v_addc_co_u32_e32 v159, vcc, 0, v153, vcc
	v_add_co_u32_e32 v160, vcc, s3, v150
	s_waitcnt lgkmcnt(9)
	v_mfma_f32_32x32x16_bf16 v[32:47], v[228:231], v[244:247], v[32:47]
	global_load_dwordx4 v[98:101], v[152:153], off offset:384
	global_load_dwordx4 v[102:105], v[154:155], off offset:384
	v_addc_co_u32_e32 v161, vcc, 0, v151, vcc
	v_add_co_u32_e32 v170, vcc, s7, v150
	global_load_dwordx4 v[106:109], v[156:157], off offset:384
	s_waitcnt lgkmcnt(8)
	v_mfma_f32_32x32x16_bf16 v[16:31], v[224:227], v[212:215], v[16:31]
	s_nop 0
	v_addc_co_u32_e32 v171, vcc, 0, v151, vcc
	v_add_co_u32_e32 v172, vcc, s8, v150
	global_load_dwordx4 v[110:113], v[158:159], off offset:384
	global_load_dwordx4 v[114:117], v[150:151], off offset:384
	v_mfma_f32_32x32x16_bf16 v[0:15], v[224:227], v[244:247], v[0:15]
	v_addc_co_u32_e32 v173, vcc, 0, v151, vcc
	global_load_dwordx4 v[118:121], v[160:161], off offset:384
	global_load_dwordx4 v[122:125], v[170:171], off offset:384
	global_load_dwordx4 v[130:133], v[172:173], off offset:384
	s_setprio 0
	s_waitcnt lgkmcnt(0)
	s_barrier
	s_setprio 1
	ds_read_b128 v[212:215], v96 offset:55296
	ds_read_b128 v[216:219], v178 offset:18432
	ds_read_b128 v[220:223], v178 offset:23040
	ds_read_b128 v[224:227], v96 offset:59904
	ds_read_b128 v[228:231], v96 offset:55328
	ds_read_b128 v[244:247], v178 offset:18464
	ds_read_b128 v[252:255], v178 offset:23072
	s_waitcnt lgkmcnt(5)
	v_mfma_f32_32x32x16_bf16 v[48:63], v[212:215], v[216:219], v[48:63]
	s_waitcnt lgkmcnt(4)
	v_mfma_f32_32x32x16_bf16 v[32:47], v[212:215], v[220:223], v[32:47]
	ds_read_b128 v[212:215], v96 offset:59936
	s_waitcnt lgkmcnt(4)
	v_mfma_f32_32x32x16_bf16 v[16:31], v[224:227], v[216:219], v[16:31]
	ds_read_b128 v[216:219], v96 offset:55360
	v_mfma_f32_32x32x16_bf16 v[0:15], v[224:227], v[220:223], v[0:15]
	ds_read_b128 v[224:227], v178 offset:18496
	ds_read_b128 v[220:223], v178 offset:23104
	s_waitcnt lgkmcnt(5)
	v_mfma_f32_32x32x16_bf16 v[48:63], v[228:231], v[244:247], v[48:63]
	s_waitcnt lgkmcnt(4)
	v_mfma_f32_32x32x16_bf16 v[32:47], v[228:231], v[252:255], v[32:47]
	ds_read_b128 v[228:231], v96 offset:59968
	s_waitcnt lgkmcnt(4)
	v_mfma_f32_32x32x16_bf16 v[16:31], v[212:215], v[244:247], v[16:31]
	ds_read_b128 v[244:247], v96 offset:55392
	v_mfma_f32_32x32x16_bf16 v[0:15], v[212:215], v[252:255], v[0:15]
	ds_read_b128 v[212:215], v178 offset:18528
	ds_read_b128 v[252:255], v178 offset:23136
	s_waitcnt lgkmcnt(5)
	v_mfma_f32_32x32x16_bf16 v[48:63], v[216:219], v[224:227], v[48:63]
	s_waitcnt vmcnt(15)
	ds_write_b128 v177, v[64:67]
	global_load_dwordx4 v[64:67], v[152:153], off offset:512
	s_waitcnt lgkmcnt(5)
	v_mfma_f32_32x32x16_bf16 v[32:47], v[216:219], v[220:223], v[32:47]
	ds_read_b128 v[216:219], v96 offset:60000
	s_waitcnt vmcnt(15)
	ds_write_b128 v177, v[68:71] offset:4608
	s_waitcnt vmcnt(14)
	ds_write_b128 v177, v[72:75] offset:9216
	s_waitcnt lgkmcnt(7)
	v_mfma_f32_32x32x16_bf16 v[16:31], v[228:231], v[224:227], v[16:31]
	global_load_dwordx4 v[72:75], v[154:155], off offset:512
	s_waitcnt vmcnt(14)
	ds_write_b128 v177, v[76:79] offset:13824
	v_mfma_f32_32x32x16_bf16 v[0:15], v[228:231], v[220:223], v[0:15]
	global_load_dwordx4 v[76:79], v[156:157], off offset:512
	s_waitcnt vmcnt(14)
	ds_write_b128 v177, v[80:83] offset:36864
	s_waitcnt lgkmcnt(7)
	v_mfma_f32_32x32x16_bf16 v[48:63], v[244:247], v[212:215], v[48:63]
	global_load_dwordx4 v[80:83], v[158:159], off offset:512
	global_load_dwordx4 v[126:129], v[150:151], off offset:512
	s_waitcnt lgkmcnt(6)
	v_mfma_f32_32x32x16_bf16 v[32:47], v[244:247], v[252:255], v[32:47]
	s_waitcnt vmcnt(15)
	ds_write_b128 v177, v[84:87] offset:41472
	global_load_dwordx4 v[134:137], v[160:161], off offset:512
	s_waitcnt lgkmcnt(5)
	v_mfma_f32_32x32x16_bf16 v[16:31], v[216:219], v[212:215], v[16:31]
	s_waitcnt vmcnt(15)
	ds_write_b128 v177, v[88:91] offset:46080
	global_load_dwordx4 v[138:141], v[170:171], off offset:512
	v_mfma_f32_32x32x16_bf16 v[0:15], v[216:219], v[252:255], v[0:15]
	s_waitcnt vmcnt(15)
	ds_write_b128 v177, v[92:95] offset:50688
	global_load_dwordx4 v[142:145], v[172:173], off offset:512
	s_setprio 0
	s_waitcnt lgkmcnt(0)
	s_barrier
	s_setprio 1
	ds_read_b128 v[212:215], v96 offset:36864
	ds_read_b128 v[216:219], v178
	ds_read_b128 v[220:223], v178 offset:4608
	ds_read_b128 v[224:227], v96 offset:41472
	ds_read_b128 v[228:231], v96 offset:36896
	ds_read_b128 v[244:247], v178 offset:32
	ds_read_b128 v[252:255], v178 offset:4640
	s_waitcnt lgkmcnt(5)
	v_mfma_f32_32x32x16_bf16 v[48:63], v[212:215], v[216:219], v[48:63]
	s_waitcnt lgkmcnt(4)
	v_mfma_f32_32x32x16_bf16 v[32:47], v[212:215], v[220:223], v[32:47]
	ds_read_b128 v[212:215], v96 offset:41504
	s_waitcnt lgkmcnt(4)
	v_mfma_f32_32x32x16_bf16 v[16:31], v[224:227], v[216:219], v[16:31]
	ds_read_b128 v[216:219], v96 offset:36928
	v_mfma_f32_32x32x16_bf16 v[0:15], v[224:227], v[220:223], v[0:15]
	ds_read_b128 v[224:227], v178 offset:64
	ds_read_b128 v[220:223], v178 offset:4672
	s_waitcnt lgkmcnt(5)
	v_mfma_f32_32x32x16_bf16 v[48:63], v[228:231], v[244:247], v[48:63]
	s_waitcnt lgkmcnt(4)
	v_mfma_f32_32x32x16_bf16 v[32:47], v[228:231], v[252:255], v[32:47]
	ds_read_b128 v[228:231], v96 offset:41536
	s_waitcnt lgkmcnt(4)
	v_mfma_f32_32x32x16_bf16 v[16:31], v[212:215], v[244:247], v[16:31]
	ds_read_b128 v[244:247], v96 offset:36960
	v_mfma_f32_32x32x16_bf16 v[0:15], v[212:215], v[252:255], v[0:15]
	ds_read_b128 v[212:215], v178 offset:96
	ds_read_b128 v[252:255], v178 offset:4704
	s_waitcnt lgkmcnt(5)
	v_mfma_f32_32x32x16_bf16 v[48:63], v[216:219], v[224:227], v[48:63]
	s_waitcnt vmcnt(15)
	ds_write_b128 v177, v[98:101] offset:18432
	global_load_dwordx4 v[68:71], v[152:153], off offset:640
	s_waitcnt lgkmcnt(5)
	v_mfma_f32_32x32x16_bf16 v[32:47], v[216:219], v[220:223], v[32:47]
	ds_read_b128 v[216:219], v96 offset:41568
	s_waitcnt vmcnt(15)
	ds_write_b128 v177, v[102:105] offset:23040
	global_load_dwordx4 v[84:87], v[154:155], off offset:640
	s_waitcnt lgkmcnt(6)
	v_mfma_f32_32x32x16_bf16 v[16:31], v[228:231], v[224:227], v[16:31]
	s_waitcnt vmcnt(15)
	ds_write_b128 v177, v[106:109] offset:27648
	global_load_dwordx4 v[88:91], v[156:157], off offset:640
	v_mfma_f32_32x32x16_bf16 v[0:15], v[228:231], v[220:223], v[0:15]
	s_waitcnt vmcnt(15)
	ds_write_b128 v177, v[110:113] offset:32256
	global_load_dwordx4 v[92:95], v[158:159], off offset:640
	s_waitcnt lgkmcnt(6)
	v_mfma_f32_32x32x16_bf16 v[48:63], v[244:247], v[212:215], v[48:63]
	s_waitcnt vmcnt(15)
	ds_write_b128 v177, v[114:117] offset:55296
	global_load_dwordx4 v[98:101], v[150:151], off offset:640
	s_waitcnt lgkmcnt(6)
	v_mfma_f32_32x32x16_bf16 v[32:47], v[244:247], v[252:255], v[32:47]
	s_waitcnt vmcnt(15)
	ds_write_b128 v177, v[118:121] offset:59904
	global_load_dwordx4 v[106:109], v[160:161], off offset:640
	s_waitcnt lgkmcnt(5)
	v_mfma_f32_32x32x16_bf16 v[16:31], v[216:219], v[212:215], v[16:31]
	s_waitcnt vmcnt(15)
	ds_write_b128 v177, v[122:125] offset:64512
	global_load_dwordx4 v[110:113], v[170:171], off offset:640
	v_mfma_f32_32x32x16_bf16 v[0:15], v[216:219], v[252:255], v[0:15]
	s_waitcnt vmcnt(15)
	ds_write_b128 v179, v[130:133] offset:13824
	global_load_dwordx4 v[114:117], v[172:173], off offset:640
	s_setprio 0
	s_waitcnt lgkmcnt(0)
	s_barrier
	s_setprio 1
	ds_read_b128 v[212:215], v96 offset:55296
	ds_read_b128 v[216:219], v178 offset:18432
	ds_read_b128 v[220:223], v178 offset:23040
	ds_read_b128 v[224:227], v96 offset:59904
	ds_read_b128 v[228:231], v96 offset:55328
	ds_read_b128 v[244:247], v178 offset:18464
	ds_read_b128 v[252:255], v178 offset:23072
	s_waitcnt lgkmcnt(5)
	v_mfma_f32_32x32x16_bf16 v[48:63], v[212:215], v[216:219], v[48:63]
	s_waitcnt lgkmcnt(4)
	v_mfma_f32_32x32x16_bf16 v[32:47], v[212:215], v[220:223], v[32:47]
	ds_read_b128 v[212:215], v96 offset:59936
	s_waitcnt lgkmcnt(4)
	v_mfma_f32_32x32x16_bf16 v[16:31], v[224:227], v[216:219], v[16:31]
	ds_read_b128 v[216:219], v96 offset:55360
	v_mfma_f32_32x32x16_bf16 v[0:15], v[224:227], v[220:223], v[0:15]
	ds_read_b128 v[224:227], v178 offset:18496
	ds_read_b128 v[220:223], v178 offset:23104
	s_waitcnt lgkmcnt(5)
	v_mfma_f32_32x32x16_bf16 v[48:63], v[228:231], v[244:247], v[48:63]
	s_waitcnt lgkmcnt(4)
	v_mfma_f32_32x32x16_bf16 v[32:47], v[228:231], v[252:255], v[32:47]
	ds_read_b128 v[228:231], v96 offset:59968
	s_waitcnt lgkmcnt(4)
	v_mfma_f32_32x32x16_bf16 v[16:31], v[212:215], v[244:247], v[16:31]
	ds_read_b128 v[244:247], v96 offset:55392
	v_mfma_f32_32x32x16_bf16 v[0:15], v[212:215], v[252:255], v[0:15]
	ds_read_b128 v[212:215], v178 offset:18528
	ds_read_b128 v[252:255], v178 offset:23136
	s_waitcnt lgkmcnt(5)
	v_mfma_f32_32x32x16_bf16 v[48:63], v[216:219], v[224:227], v[48:63]
	s_waitcnt vmcnt(15)
	ds_write_b128 v177, v[64:67]
	global_load_dwordx4 v[64:67], v[152:153], off offset:768
	s_waitcnt lgkmcnt(5)
	v_mfma_f32_32x32x16_bf16 v[32:47], v[216:219], v[220:223], v[32:47]
	ds_read_b128 v[216:219], v96 offset:60000
	s_waitcnt vmcnt(15)
	ds_write_b128 v177, v[72:75] offset:4608
	global_load_dwordx4 v[72:75], v[154:155], off offset:768
	s_waitcnt lgkmcnt(6)
	v_mfma_f32_32x32x16_bf16 v[16:31], v[228:231], v[224:227], v[16:31]
	s_waitcnt vmcnt(15)
	ds_write_b128 v177, v[76:79] offset:9216
	global_load_dwordx4 v[76:79], v[156:157], off offset:768
	v_mfma_f32_32x32x16_bf16 v[0:15], v[228:231], v[220:223], v[0:15]
	s_waitcnt vmcnt(15)
	ds_write_b128 v177, v[80:83] offset:13824
	global_load_dwordx4 v[80:83], v[158:159], off offset:768
	s_waitcnt lgkmcnt(6)
	v_mfma_f32_32x32x16_bf16 v[48:63], v[244:247], v[212:215], v[48:63]
	s_waitcnt vmcnt(15)
	ds_write_b128 v177, v[126:129] offset:36864
	global_load_dwordx4 v[102:105], v[150:151], off offset:768
	s_waitcnt lgkmcnt(6)
	v_mfma_f32_32x32x16_bf16 v[32:47], v[244:247], v[252:255], v[32:47]
	s_waitcnt vmcnt(15)
	ds_write_b128 v177, v[134:137] offset:41472
	global_load_dwordx4 v[118:121], v[160:161], off offset:768
	s_waitcnt lgkmcnt(5)
	v_mfma_f32_32x32x16_bf16 v[16:31], v[216:219], v[212:215], v[16:31]
	s_waitcnt vmcnt(15)
	ds_write_b128 v177, v[138:141] offset:46080
	global_load_dwordx4 v[122:125], v[170:171], off offset:768
	v_mfma_f32_32x32x16_bf16 v[0:15], v[216:219], v[252:255], v[0:15]
	s_waitcnt vmcnt(15)
	ds_write_b128 v177, v[142:145] offset:50688
	global_load_dwordx4 v[126:129], v[172:173], off offset:768
	s_setprio 0
	s_waitcnt lgkmcnt(0)
	s_barrier
	s_setprio 1
	ds_read_b128 v[212:215], v96 offset:36864
	ds_read_b128 v[216:219], v178
	ds_read_b128 v[220:223], v178 offset:4608
	ds_read_b128 v[224:227], v96 offset:41472
	ds_read_b128 v[228:231], v96 offset:36896
	ds_read_b128 v[244:247], v178 offset:32
	ds_read_b128 v[252:255], v178 offset:4640
	s_waitcnt lgkmcnt(5)
	v_mfma_f32_32x32x16_bf16 v[48:63], v[212:215], v[216:219], v[48:63]
	s_waitcnt lgkmcnt(4)
	v_mfma_f32_32x32x16_bf16 v[32:47], v[212:215], v[220:223], v[32:47]
	ds_read_b128 v[212:215], v96 offset:41504
	s_waitcnt lgkmcnt(4)
	v_mfma_f32_32x32x16_bf16 v[16:31], v[224:227], v[216:219], v[16:31]
	ds_read_b128 v[216:219], v96 offset:36928
	v_mfma_f32_32x32x16_bf16 v[0:15], v[224:227], v[220:223], v[0:15]
	ds_read_b128 v[224:227], v178 offset:64
	ds_read_b128 v[220:223], v178 offset:4672
	s_waitcnt lgkmcnt(5)
	v_mfma_f32_32x32x16_bf16 v[48:63], v[228:231], v[244:247], v[48:63]
	s_waitcnt lgkmcnt(4)
	v_mfma_f32_32x32x16_bf16 v[32:47], v[228:231], v[252:255], v[32:47]
	ds_read_b128 v[228:231], v96 offset:41536
	s_waitcnt lgkmcnt(4)
	v_mfma_f32_32x32x16_bf16 v[16:31], v[212:215], v[244:247], v[16:31]
	ds_read_b128 v[244:247], v96 offset:36960
	v_mfma_f32_32x32x16_bf16 v[0:15], v[212:215], v[252:255], v[0:15]
	ds_read_b128 v[212:215], v178 offset:96
	ds_read_b128 v[252:255], v178 offset:4704
	s_waitcnt lgkmcnt(5)
	v_mfma_f32_32x32x16_bf16 v[48:63], v[216:219], v[224:227], v[48:63]
	s_waitcnt vmcnt(15)
	ds_write_b128 v177, v[68:71] offset:18432
	global_load_dwordx4 v[68:71], v[152:153], off offset:896
	s_waitcnt lgkmcnt(5)
	v_mfma_f32_32x32x16_bf16 v[32:47], v[216:219], v[220:223], v[32:47]
	ds_read_b128 v[216:219], v96 offset:41568
	s_waitcnt vmcnt(15)
	ds_write_b128 v177, v[84:87] offset:23040
	global_load_dwordx4 v[84:87], v[154:155], off offset:896
	s_waitcnt lgkmcnt(6)
	v_mfma_f32_32x32x16_bf16 v[16:31], v[228:231], v[224:227], v[16:31]
	s_waitcnt vmcnt(15)
	ds_write_b128 v177, v[88:91] offset:27648
	global_load_dwordx4 v[88:91], v[156:157], off offset:896
	v_mfma_f32_32x32x16_bf16 v[0:15], v[228:231], v[220:223], v[0:15]
	s_waitcnt vmcnt(15)
	ds_write_b128 v177, v[92:95] offset:32256
	global_load_dwordx4 v[92:95], v[158:159], off offset:896
	s_waitcnt lgkmcnt(6)
	v_mfma_f32_32x32x16_bf16 v[48:63], v[244:247], v[212:215], v[48:63]
	s_waitcnt vmcnt(15)
	ds_write_b128 v177, v[98:101] offset:55296
	global_load_dwordx4 v[98:101], v[150:151], off offset:896
	s_waitcnt lgkmcnt(6)
	v_mfma_f32_32x32x16_bf16 v[32:47], v[244:247], v[252:255], v[32:47]
	s_waitcnt vmcnt(15)
	ds_write_b128 v177, v[106:109] offset:59904
	global_load_dwordx4 v[106:109], v[160:161], off offset:896
	s_waitcnt lgkmcnt(5)
	v_mfma_f32_32x32x16_bf16 v[16:31], v[216:219], v[212:215], v[16:31]
	s_waitcnt vmcnt(15)
	ds_write_b128 v177, v[110:113] offset:64512
	global_load_dwordx4 v[110:113], v[170:171], off offset:896
	v_mfma_f32_32x32x16_bf16 v[0:15], v[216:219], v[252:255], v[0:15]
	s_waitcnt vmcnt(15)
	ds_write_b128 v179, v[114:117] offset:13824
	global_load_dwordx4 v[114:117], v[172:173], off offset:896
	s_setprio 0
	s_waitcnt lgkmcnt(0)
	s_barrier
	s_setprio 1
	ds_read_b128 v[212:215], v96 offset:55296
	ds_read_b128 v[216:219], v178 offset:18432
	ds_read_b128 v[220:223], v178 offset:23040
	ds_read_b128 v[224:227], v96 offset:59904
	ds_read_b128 v[228:231], v96 offset:55328
	ds_read_b128 v[244:247], v178 offset:18464
	ds_read_b128 v[252:255], v178 offset:23072
	s_waitcnt lgkmcnt(5)
	v_mfma_f32_32x32x16_bf16 v[48:63], v[212:215], v[216:219], v[48:63]
	s_waitcnt lgkmcnt(4)
	v_mfma_f32_32x32x16_bf16 v[32:47], v[212:215], v[220:223], v[32:47]
	ds_read_b128 v[212:215], v96 offset:59936
	s_waitcnt lgkmcnt(4)
	v_mfma_f32_32x32x16_bf16 v[16:31], v[224:227], v[216:219], v[16:31]
	ds_read_b128 v[216:219], v96 offset:55360
	v_mfma_f32_32x32x16_bf16 v[0:15], v[224:227], v[220:223], v[0:15]
	ds_read_b128 v[224:227], v178 offset:18496
	ds_read_b128 v[220:223], v178 offset:23104
	s_waitcnt lgkmcnt(5)
	v_mfma_f32_32x32x16_bf16 v[48:63], v[228:231], v[244:247], v[48:63]
	s_waitcnt lgkmcnt(4)
	v_mfma_f32_32x32x16_bf16 v[32:47], v[228:231], v[252:255], v[32:47]
	ds_read_b128 v[228:231], v96 offset:59968
	s_waitcnt lgkmcnt(4)
	v_mfma_f32_32x32x16_bf16 v[16:31], v[212:215], v[244:247], v[16:31]
	ds_read_b128 v[244:247], v96 offset:55392
	v_mfma_f32_32x32x16_bf16 v[0:15], v[212:215], v[252:255], v[0:15]
	ds_read_b128 v[212:215], v178 offset:18528
	ds_read_b128 v[252:255], v178 offset:23136
	s_waitcnt lgkmcnt(5)
	v_mfma_f32_32x32x16_bf16 v[48:63], v[216:219], v[224:227], v[48:63]
	s_waitcnt vmcnt(15)
	ds_write_b128 v177, v[64:67]
	global_load_dwordx4 v[64:67], v[152:153], off offset:1024
	s_waitcnt lgkmcnt(5)
	v_mfma_f32_32x32x16_bf16 v[32:47], v[216:219], v[220:223], v[32:47]
	ds_read_b128 v[216:219], v96 offset:60000
	s_waitcnt vmcnt(15)
	ds_write_b128 v177, v[72:75] offset:4608
	global_load_dwordx4 v[72:75], v[154:155], off offset:1024
	s_waitcnt lgkmcnt(6)
	v_mfma_f32_32x32x16_bf16 v[16:31], v[228:231], v[224:227], v[16:31]
	s_waitcnt vmcnt(15)
	ds_write_b128 v177, v[76:79] offset:9216
	global_load_dwordx4 v[76:79], v[156:157], off offset:1024
	v_mfma_f32_32x32x16_bf16 v[0:15], v[228:231], v[220:223], v[0:15]
	s_waitcnt vmcnt(15)
	ds_write_b128 v177, v[80:83] offset:13824
	global_load_dwordx4 v[80:83], v[158:159], off offset:1024
	s_waitcnt lgkmcnt(6)
	v_mfma_f32_32x32x16_bf16 v[48:63], v[244:247], v[212:215], v[48:63]
	s_waitcnt vmcnt(15)
	ds_write_b128 v177, v[102:105] offset:36864
	global_load_dwordx4 v[102:105], v[150:151], off offset:1024
	s_waitcnt lgkmcnt(6)
	v_mfma_f32_32x32x16_bf16 v[32:47], v[244:247], v[252:255], v[32:47]
	s_waitcnt vmcnt(15)
	ds_write_b128 v177, v[118:121] offset:41472
	global_load_dwordx4 v[118:121], v[160:161], off offset:1024
	s_waitcnt lgkmcnt(5)
	v_mfma_f32_32x32x16_bf16 v[16:31], v[216:219], v[212:215], v[16:31]
	s_waitcnt vmcnt(15)
	ds_write_b128 v177, v[122:125] offset:46080
	global_load_dwordx4 v[122:125], v[170:171], off offset:1024
	v_mfma_f32_32x32x16_bf16 v[0:15], v[216:219], v[252:255], v[0:15]
	s_waitcnt vmcnt(15)
	ds_write_b128 v177, v[126:129] offset:50688
	global_load_dwordx4 v[126:129], v[172:173], off offset:1024
	s_setprio 0
	s_waitcnt lgkmcnt(0)
	s_barrier
	s_setprio 1
	ds_read_b128 v[212:215], v96 offset:36864
	ds_read_b128 v[216:219], v178
	ds_read_b128 v[220:223], v178 offset:4608
	ds_read_b128 v[224:227], v96 offset:41472
	ds_read_b128 v[228:231], v96 offset:36896
	ds_read_b128 v[244:247], v178 offset:32
	ds_read_b128 v[252:255], v178 offset:4640
	s_waitcnt lgkmcnt(5)
	v_mfma_f32_32x32x16_bf16 v[48:63], v[212:215], v[216:219], v[48:63]
	s_waitcnt lgkmcnt(4)
	v_mfma_f32_32x32x16_bf16 v[32:47], v[212:215], v[220:223], v[32:47]
	ds_read_b128 v[212:215], v96 offset:41504
	s_waitcnt lgkmcnt(4)
	v_mfma_f32_32x32x16_bf16 v[16:31], v[224:227], v[216:219], v[16:31]
	ds_read_b128 v[216:219], v96 offset:36928
	v_mfma_f32_32x32x16_bf16 v[0:15], v[224:227], v[220:223], v[0:15]
	ds_read_b128 v[224:227], v178 offset:64
	ds_read_b128 v[220:223], v178 offset:4672
	s_waitcnt lgkmcnt(5)
	v_mfma_f32_32x32x16_bf16 v[48:63], v[228:231], v[244:247], v[48:63]
	s_waitcnt lgkmcnt(4)
	v_mfma_f32_32x32x16_bf16 v[32:47], v[228:231], v[252:255], v[32:47]
	ds_read_b128 v[228:231], v96 offset:41536
	s_waitcnt lgkmcnt(4)
	v_mfma_f32_32x32x16_bf16 v[16:31], v[212:215], v[244:247], v[16:31]
	ds_read_b128 v[244:247], v96 offset:36960
	v_mfma_f32_32x32x16_bf16 v[0:15], v[212:215], v[252:255], v[0:15]
	ds_read_b128 v[212:215], v178 offset:96
	ds_read_b128 v[252:255], v178 offset:4704
	s_waitcnt lgkmcnt(5)
	v_mfma_f32_32x32x16_bf16 v[48:63], v[216:219], v[224:227], v[48:63]
	s_waitcnt vmcnt(15)
	ds_write_b128 v177, v[68:71] offset:18432
	global_load_dwordx4 v[68:71], v[152:153], off offset:1152
	s_waitcnt lgkmcnt(5)
	v_mfma_f32_32x32x16_bf16 v[32:47], v[216:219], v[220:223], v[32:47]
	ds_read_b128 v[216:219], v96 offset:41568
	s_waitcnt vmcnt(15)
	ds_write_b128 v177, v[84:87] offset:23040
	global_load_dwordx4 v[84:87], v[154:155], off offset:1152
	s_waitcnt lgkmcnt(6)
	v_mfma_f32_32x32x16_bf16 v[16:31], v[228:231], v[224:227], v[16:31]
	s_waitcnt vmcnt(15)
	ds_write_b128 v177, v[88:91] offset:27648
	global_load_dwordx4 v[88:91], v[156:157], off offset:1152
	v_mfma_f32_32x32x16_bf16 v[0:15], v[228:231], v[220:223], v[0:15]
	s_waitcnt vmcnt(15)
	ds_write_b128 v177, v[92:95] offset:32256
	global_load_dwordx4 v[92:95], v[158:159], off offset:1152
	s_waitcnt lgkmcnt(6)
	v_mfma_f32_32x32x16_bf16 v[48:63], v[244:247], v[212:215], v[48:63]
	s_waitcnt vmcnt(15)
	ds_write_b128 v177, v[98:101] offset:55296
	global_load_dwordx4 v[98:101], v[150:151], off offset:1152
	s_waitcnt lgkmcnt(6)
	v_mfma_f32_32x32x16_bf16 v[32:47], v[244:247], v[252:255], v[32:47]
	s_waitcnt vmcnt(15)
	ds_write_b128 v177, v[106:109] offset:59904
	global_load_dwordx4 v[106:109], v[160:161], off offset:1152
	s_waitcnt lgkmcnt(5)
	v_mfma_f32_32x32x16_bf16 v[16:31], v[216:219], v[212:215], v[16:31]
	s_waitcnt vmcnt(15)
	ds_write_b128 v177, v[110:113] offset:64512
	global_load_dwordx4 v[110:113], v[170:171], off offset:1152
	v_mfma_f32_32x32x16_bf16 v[0:15], v[216:219], v[252:255], v[0:15]
	s_waitcnt vmcnt(15)
	ds_write_b128 v179, v[114:117] offset:13824
	global_load_dwordx4 v[114:117], v[172:173], off offset:1152
	s_setprio 0
	s_waitcnt lgkmcnt(0)
	s_barrier
	s_setprio 1
	ds_read_b128 v[212:215], v96 offset:55296
	ds_read_b128 v[216:219], v178 offset:18432
	ds_read_b128 v[220:223], v178 offset:23040
	ds_read_b128 v[224:227], v96 offset:59904
	ds_read_b128 v[228:231], v96 offset:55328
	ds_read_b128 v[244:247], v178 offset:18464
	ds_read_b128 v[252:255], v178 offset:23072
	s_waitcnt lgkmcnt(5)
	v_mfma_f32_32x32x16_bf16 v[48:63], v[212:215], v[216:219], v[48:63]
	s_waitcnt lgkmcnt(4)
	v_mfma_f32_32x32x16_bf16 v[32:47], v[212:215], v[220:223], v[32:47]
	ds_read_b128 v[212:215], v96 offset:59936
	s_waitcnt lgkmcnt(4)
	v_mfma_f32_32x32x16_bf16 v[16:31], v[224:227], v[216:219], v[16:31]
	ds_read_b128 v[216:219], v96 offset:55360
	v_mfma_f32_32x32x16_bf16 v[0:15], v[224:227], v[220:223], v[0:15]
	ds_read_b128 v[224:227], v178 offset:18496
	ds_read_b128 v[220:223], v178 offset:23104
	s_waitcnt lgkmcnt(5)
	v_mfma_f32_32x32x16_bf16 v[48:63], v[228:231], v[244:247], v[48:63]
	s_waitcnt lgkmcnt(4)
	v_mfma_f32_32x32x16_bf16 v[32:47], v[228:231], v[252:255], v[32:47]
	ds_read_b128 v[228:231], v96 offset:59968
	s_waitcnt lgkmcnt(4)
	v_mfma_f32_32x32x16_bf16 v[16:31], v[212:215], v[244:247], v[16:31]
	ds_read_b128 v[244:247], v96 offset:55392
	v_mfma_f32_32x32x16_bf16 v[0:15], v[212:215], v[252:255], v[0:15]
	ds_read_b128 v[212:215], v178 offset:18528
	ds_read_b128 v[252:255], v178 offset:23136
	s_waitcnt lgkmcnt(5)
	v_mfma_f32_32x32x16_bf16 v[48:63], v[216:219], v[224:227], v[48:63]
	s_waitcnt vmcnt(15)
	ds_write_b128 v177, v[64:67]
	global_load_dwordx4 v[64:67], v[152:153], off offset:1280
	s_waitcnt lgkmcnt(5)
	v_mfma_f32_32x32x16_bf16 v[32:47], v[216:219], v[220:223], v[32:47]
	ds_read_b128 v[216:219], v96 offset:60000
	s_waitcnt vmcnt(15)
	ds_write_b128 v177, v[72:75] offset:4608
	global_load_dwordx4 v[72:75], v[154:155], off offset:1280
	s_waitcnt lgkmcnt(6)
	v_mfma_f32_32x32x16_bf16 v[16:31], v[228:231], v[224:227], v[16:31]
	s_waitcnt vmcnt(15)
	ds_write_b128 v177, v[76:79] offset:9216
	global_load_dwordx4 v[76:79], v[156:157], off offset:1280
	v_mfma_f32_32x32x16_bf16 v[0:15], v[228:231], v[220:223], v[0:15]
	s_waitcnt vmcnt(15)
	ds_write_b128 v177, v[80:83] offset:13824
	global_load_dwordx4 v[80:83], v[158:159], off offset:1280
	s_waitcnt lgkmcnt(6)
	v_mfma_f32_32x32x16_bf16 v[48:63], v[244:247], v[212:215], v[48:63]
	s_waitcnt vmcnt(15)
	ds_write_b128 v177, v[102:105] offset:36864
	global_load_dwordx4 v[102:105], v[150:151], off offset:1280
	s_waitcnt lgkmcnt(6)
	v_mfma_f32_32x32x16_bf16 v[32:47], v[244:247], v[252:255], v[32:47]
	s_waitcnt vmcnt(15)
	ds_write_b128 v177, v[118:121] offset:41472
	global_load_dwordx4 v[118:121], v[160:161], off offset:1280
	s_waitcnt lgkmcnt(5)
	v_mfma_f32_32x32x16_bf16 v[16:31], v[216:219], v[212:215], v[16:31]
	s_waitcnt vmcnt(15)
	ds_write_b128 v177, v[122:125] offset:46080
	global_load_dwordx4 v[122:125], v[170:171], off offset:1280
	v_mfma_f32_32x32x16_bf16 v[0:15], v[216:219], v[252:255], v[0:15]
	s_waitcnt vmcnt(15)
	ds_write_b128 v177, v[126:129] offset:50688
	global_load_dwordx4 v[126:129], v[172:173], off offset:1280
	s_setprio 0
	s_waitcnt lgkmcnt(0)
	s_barrier
	s_setprio 1
	ds_read_b128 v[212:215], v96 offset:36864
	ds_read_b128 v[216:219], v178
	ds_read_b128 v[220:223], v178 offset:4608
	ds_read_b128 v[224:227], v96 offset:41472
	ds_read_b128 v[228:231], v96 offset:36896
	ds_read_b128 v[244:247], v178 offset:32
	ds_read_b128 v[252:255], v178 offset:4640
	s_waitcnt lgkmcnt(5)
	v_mfma_f32_32x32x16_bf16 v[48:63], v[212:215], v[216:219], v[48:63]
	s_waitcnt lgkmcnt(4)
	v_mfma_f32_32x32x16_bf16 v[32:47], v[212:215], v[220:223], v[32:47]
	ds_read_b128 v[212:215], v96 offset:41504
	s_waitcnt lgkmcnt(4)
	v_mfma_f32_32x32x16_bf16 v[16:31], v[224:227], v[216:219], v[16:31]
	ds_read_b128 v[216:219], v96 offset:36928
	v_mfma_f32_32x32x16_bf16 v[0:15], v[224:227], v[220:223], v[0:15]
	ds_read_b128 v[224:227], v178 offset:64
	ds_read_b128 v[220:223], v178 offset:4672
	s_waitcnt lgkmcnt(5)
	v_mfma_f32_32x32x16_bf16 v[48:63], v[228:231], v[244:247], v[48:63]
	s_waitcnt lgkmcnt(4)
	v_mfma_f32_32x32x16_bf16 v[32:47], v[228:231], v[252:255], v[32:47]
	ds_read_b128 v[228:231], v96 offset:41536
	s_waitcnt lgkmcnt(4)
	v_mfma_f32_32x32x16_bf16 v[16:31], v[212:215], v[244:247], v[16:31]
	ds_read_b128 v[244:247], v96 offset:36960
	v_mfma_f32_32x32x16_bf16 v[0:15], v[212:215], v[252:255], v[0:15]
	ds_read_b128 v[212:215], v178 offset:96
	ds_read_b128 v[252:255], v178 offset:4704
	s_waitcnt lgkmcnt(5)
	v_mfma_f32_32x32x16_bf16 v[48:63], v[216:219], v[224:227], v[48:63]
	s_waitcnt vmcnt(15)
	ds_write_b128 v177, v[68:71] offset:18432
	global_load_dwordx4 v[68:71], v[152:153], off offset:1408
	s_waitcnt lgkmcnt(5)
	v_mfma_f32_32x32x16_bf16 v[32:47], v[216:219], v[220:223], v[32:47]
	ds_read_b128 v[216:219], v96 offset:41568
	s_waitcnt vmcnt(15)
	ds_write_b128 v177, v[84:87] offset:23040
	global_load_dwordx4 v[84:87], v[154:155], off offset:1408
	s_waitcnt lgkmcnt(6)
	v_mfma_f32_32x32x16_bf16 v[16:31], v[228:231], v[224:227], v[16:31]
	s_waitcnt vmcnt(15)
	ds_write_b128 v177, v[88:91] offset:27648
	global_load_dwordx4 v[88:91], v[156:157], off offset:1408
	v_mfma_f32_32x32x16_bf16 v[0:15], v[228:231], v[220:223], v[0:15]
	s_waitcnt vmcnt(15)
	ds_write_b128 v177, v[92:95] offset:32256
	global_load_dwordx4 v[92:95], v[158:159], off offset:1408
	s_waitcnt lgkmcnt(6)
	v_mfma_f32_32x32x16_bf16 v[48:63], v[244:247], v[212:215], v[48:63]
	s_waitcnt vmcnt(15)
	ds_write_b128 v177, v[98:101] offset:55296
	global_load_dwordx4 v[98:101], v[150:151], off offset:1408
	s_waitcnt lgkmcnt(6)
	v_mfma_f32_32x32x16_bf16 v[32:47], v[244:247], v[252:255], v[32:47]
	s_waitcnt vmcnt(15)
	ds_write_b128 v177, v[106:109] offset:59904
	global_load_dwordx4 v[106:109], v[160:161], off offset:1408
	s_waitcnt lgkmcnt(5)
	v_mfma_f32_32x32x16_bf16 v[16:31], v[216:219], v[212:215], v[16:31]
	s_waitcnt vmcnt(15)
	ds_write_b128 v177, v[110:113] offset:64512
	global_load_dwordx4 v[110:113], v[170:171], off offset:1408
	v_mfma_f32_32x32x16_bf16 v[0:15], v[216:219], v[252:255], v[0:15]
	s_waitcnt vmcnt(15)
	ds_write_b128 v179, v[114:117] offset:13824
	global_load_dwordx4 v[130:133], v[172:173], off offset:1408
	s_setprio 0
	s_waitcnt lgkmcnt(0)
	s_barrier
	s_setprio 1
	ds_read_b128 v[212:215], v96 offset:55296
	ds_read_b128 v[216:219], v178 offset:18432
	ds_read_b128 v[220:223], v178 offset:23040
	ds_read_b128 v[224:227], v96 offset:59904
	ds_read_b128 v[228:231], v96 offset:55328
	ds_read_b128 v[244:247], v178 offset:18464
	ds_read_b128 v[252:255], v178 offset:23072
	s_waitcnt lgkmcnt(5)
	v_mfma_f32_32x32x16_bf16 v[48:63], v[212:215], v[216:219], v[48:63]
	s_waitcnt lgkmcnt(4)
	v_mfma_f32_32x32x16_bf16 v[32:47], v[212:215], v[220:223], v[32:47]
	ds_read_b128 v[212:215], v96 offset:59936
	s_waitcnt lgkmcnt(4)
	v_mfma_f32_32x32x16_bf16 v[16:31], v[224:227], v[216:219], v[16:31]
	ds_read_b128 v[216:219], v96 offset:55360
	v_mfma_f32_32x32x16_bf16 v[0:15], v[224:227], v[220:223], v[0:15]
	ds_read_b128 v[224:227], v178 offset:18496
	ds_read_b128 v[220:223], v178 offset:23104
	s_waitcnt lgkmcnt(5)
	v_mfma_f32_32x32x16_bf16 v[48:63], v[228:231], v[244:247], v[48:63]
	s_waitcnt lgkmcnt(4)
	v_mfma_f32_32x32x16_bf16 v[32:47], v[228:231], v[252:255], v[32:47]
	ds_read_b128 v[228:231], v96 offset:59968
	s_waitcnt lgkmcnt(4)
	v_mfma_f32_32x32x16_bf16 v[16:31], v[212:215], v[244:247], v[16:31]
	ds_read_b128 v[244:247], v96 offset:55392
	v_mfma_f32_32x32x16_bf16 v[0:15], v[212:215], v[252:255], v[0:15]
	ds_read_b128 v[212:215], v178 offset:18528
	ds_read_b128 v[252:255], v178 offset:23136
	s_waitcnt lgkmcnt(5)
	v_mfma_f32_32x32x16_bf16 v[48:63], v[216:219], v[224:227], v[48:63]
	s_waitcnt vmcnt(15)
	ds_write_b128 v177, v[64:67]
	global_load_dwordx4 v[64:67], v[152:153], off offset:1536
	s_waitcnt lgkmcnt(5)
	v_mfma_f32_32x32x16_bf16 v[32:47], v[216:219], v[220:223], v[32:47]
	ds_read_b128 v[216:219], v96 offset:60000
	s_waitcnt vmcnt(15)
	ds_write_b128 v177, v[72:75] offset:4608
	global_load_dwordx4 v[72:75], v[154:155], off offset:1536
	s_waitcnt lgkmcnt(6)
	v_mfma_f32_32x32x16_bf16 v[16:31], v[228:231], v[224:227], v[16:31]
	s_waitcnt vmcnt(15)
	ds_write_b128 v177, v[76:79] offset:9216
	global_load_dwordx4 v[76:79], v[156:157], off offset:1536
	v_mfma_f32_32x32x16_bf16 v[0:15], v[228:231], v[220:223], v[0:15]
	s_waitcnt vmcnt(15)
	ds_write_b128 v177, v[80:83] offset:13824
	global_load_dwordx4 v[80:83], v[158:159], off offset:1536
	s_waitcnt lgkmcnt(6)
	v_mfma_f32_32x32x16_bf16 v[48:63], v[244:247], v[212:215], v[48:63]
	s_waitcnt vmcnt(15)
	ds_write_b128 v177, v[102:105] offset:36864
	global_load_dwordx4 v[114:117], v[150:151], off offset:1536
	s_waitcnt lgkmcnt(6)
	v_mfma_f32_32x32x16_bf16 v[32:47], v[244:247], v[252:255], v[32:47]
	s_waitcnt vmcnt(15)
	ds_write_b128 v177, v[118:121] offset:41472
	s_waitcnt vmcnt(14)
	ds_write_b128 v177, v[122:125] offset:46080
	s_waitcnt lgkmcnt(6)
	v_mfma_f32_32x32x16_bf16 v[16:31], v[216:219], v[212:215], v[16:31]
	global_load_dwordx4 v[122:125], v[160:161], off offset:1536
	s_waitcnt vmcnt(14)
	ds_write_b128 v177, v[126:129] offset:50688
	v_mfma_f32_32x32x16_bf16 v[0:15], v[216:219], v[252:255], v[0:15]
	global_load_dwordx4 v[126:129], v[170:171], off offset:1536
	global_load_dwordx4 v[134:137], v[172:173], off offset:1536
	s_setprio 0
	s_waitcnt lgkmcnt(0)
	s_barrier
	s_setprio 1
	ds_read_b128 v[212:215], v96 offset:36864
	ds_read_b128 v[216:219], v178
	ds_read_b128 v[220:223], v178 offset:4608
	ds_read_b128 v[224:227], v96 offset:41472
	ds_read_b128 v[228:231], v96 offset:36896
	ds_read_b128 v[244:247], v178 offset:32
	ds_read_b128 v[252:255], v178 offset:4640
	s_waitcnt lgkmcnt(5)
	v_mfma_f32_32x32x16_bf16 v[48:63], v[212:215], v[216:219], v[48:63]
	s_waitcnt lgkmcnt(4)
	v_mfma_f32_32x32x16_bf16 v[32:47], v[212:215], v[220:223], v[32:47]
	ds_read_b128 v[212:215], v96 offset:41504
	s_waitcnt lgkmcnt(4)
	v_mfma_f32_32x32x16_bf16 v[16:31], v[224:227], v[216:219], v[16:31]
	ds_read_b128 v[216:219], v96 offset:36928
	v_mfma_f32_32x32x16_bf16 v[0:15], v[224:227], v[220:223], v[0:15]
	ds_read_b128 v[224:227], v178 offset:64
	ds_read_b128 v[220:223], v178 offset:4672
	s_waitcnt lgkmcnt(5)
	v_mfma_f32_32x32x16_bf16 v[48:63], v[228:231], v[244:247], v[48:63]
	s_waitcnt lgkmcnt(4)
	v_mfma_f32_32x32x16_bf16 v[32:47], v[228:231], v[252:255], v[32:47]
	ds_read_b128 v[228:231], v96 offset:41536
	s_waitcnt lgkmcnt(4)
	v_mfma_f32_32x32x16_bf16 v[16:31], v[212:215], v[244:247], v[16:31]
	ds_read_b128 v[244:247], v96 offset:36960
	v_mfma_f32_32x32x16_bf16 v[0:15], v[212:215], v[252:255], v[0:15]
	ds_read_b128 v[212:215], v178 offset:96
	ds_read_b128 v[252:255], v178 offset:4704
	s_waitcnt lgkmcnt(5)
	v_mfma_f32_32x32x16_bf16 v[48:63], v[216:219], v[224:227], v[48:63]
	s_waitcnt vmcnt(15)
	ds_write_b128 v177, v[68:71] offset:18432
	s_waitcnt vmcnt(14)
	ds_write_b128 v177, v[84:87] offset:23040
	s_waitcnt lgkmcnt(6)
	v_mfma_f32_32x32x16_bf16 v[32:47], v[216:219], v[220:223], v[32:47]
	ds_read_b128 v[216:219], v96 offset:41568
	s_waitcnt vmcnt(13)
	ds_write_b128 v177, v[88:91] offset:27648
	s_waitcnt vmcnt(12)
	ds_write_b128 v177, v[92:95] offset:32256
	s_waitcnt lgkmcnt(8)
	v_mfma_f32_32x32x16_bf16 v[16:31], v[228:231], v[224:227], v[16:31]
	s_waitcnt vmcnt(11)
	ds_write_b128 v177, v[98:101] offset:55296
	v_mfma_f32_32x32x16_bf16 v[0:15], v[228:231], v[220:223], v[0:15]
	global_load_dwordx4 v[98:101], v[152:153], off offset:1664
	global_load_dwordx4 v[102:105], v[154:155], off offset:1664
	s_waitcnt vmcnt(12)
	ds_write_b128 v177, v[106:109] offset:59904
	s_waitcnt lgkmcnt(8)
	v_mfma_f32_32x32x16_bf16 v[48:63], v[244:247], v[212:215], v[48:63]
	global_load_dwordx4 v[106:109], v[156:157], off offset:1664
	s_waitcnt vmcnt(12)
	ds_write_b128 v177, v[110:113] offset:64512
	s_waitcnt lgkmcnt(8)
	v_mfma_f32_32x32x16_bf16 v[32:47], v[244:247], v[252:255], v[32:47]
	global_load_dwordx4 v[110:113], v[158:159], off offset:1664
	global_load_dwordx4 v[118:121], v[150:151], off offset:1664
	s_waitcnt lgkmcnt(5)
	v_mfma_f32_32x32x16_bf16 v[16:31], v[216:219], v[212:215], v[16:31]
	s_waitcnt vmcnt(13)
	ds_write_b128 v179, v[130:133] offset:13824
	global_load_dwordx4 v[130:133], v[160:161], off offset:1664
	v_mfma_f32_32x32x16_bf16 v[0:15], v[216:219], v[252:255], v[0:15]
	global_load_dwordx4 v[138:141], v[170:171], off offset:1664
	global_load_dwordx4 v[142:145], v[172:173], off offset:1664
	s_setprio 0
	s_waitcnt lgkmcnt(0)
	s_barrier
	s_setprio 1
	ds_read_b128 v[212:215], v96 offset:55296
	ds_read_b128 v[216:219], v178 offset:18432
	ds_read_b128 v[220:223], v178 offset:23040
	ds_read_b128 v[224:227], v96 offset:59904
	ds_read_b128 v[228:231], v96 offset:55328
	ds_read_b128 v[244:247], v178 offset:18464
	ds_read_b128 v[252:255], v178 offset:23072
	s_waitcnt lgkmcnt(5)
	v_mfma_f32_32x32x16_bf16 v[48:63], v[212:215], v[216:219], v[48:63]
	s_waitcnt lgkmcnt(4)
	v_mfma_f32_32x32x16_bf16 v[32:47], v[212:215], v[220:223], v[32:47]
	ds_read_b128 v[212:215], v96 offset:59936
	s_waitcnt lgkmcnt(4)
	v_mfma_f32_32x32x16_bf16 v[16:31], v[224:227], v[216:219], v[16:31]
	ds_read_b128 v[216:219], v96 offset:55360
	v_mfma_f32_32x32x16_bf16 v[0:15], v[224:227], v[220:223], v[0:15]
	ds_read_b128 v[224:227], v178 offset:18496
	ds_read_b128 v[220:223], v178 offset:23104
	s_waitcnt lgkmcnt(5)
	v_mfma_f32_32x32x16_bf16 v[48:63], v[228:231], v[244:247], v[48:63]
	s_waitcnt lgkmcnt(4)
	v_mfma_f32_32x32x16_bf16 v[32:47], v[228:231], v[252:255], v[32:47]
	ds_read_b128 v[228:231], v96 offset:59968
	s_waitcnt lgkmcnt(4)
	v_mfma_f32_32x32x16_bf16 v[16:31], v[212:215], v[244:247], v[16:31]
	ds_read_b128 v[244:247], v96 offset:55392
	v_mfma_f32_32x32x16_bf16 v[0:15], v[212:215], v[252:255], v[0:15]
	ds_read_b128 v[212:215], v178 offset:18528
	ds_read_b128 v[252:255], v178 offset:23136
	s_waitcnt lgkmcnt(5)
	v_mfma_f32_32x32x16_bf16 v[48:63], v[216:219], v[224:227], v[48:63]
	s_waitcnt vmcnt(15)
	ds_write_b128 v177, v[64:67]
	global_load_dwordx4 v[64:67], v[152:153], off offset:1792
	s_waitcnt lgkmcnt(5)
	v_mfma_f32_32x32x16_bf16 v[32:47], v[216:219], v[220:223], v[32:47]
	ds_read_b128 v[216:219], v96 offset:60000
	s_waitcnt vmcnt(15)
	ds_write_b128 v177, v[72:75] offset:4608
	global_load_dwordx4 v[68:71], v[154:155], off offset:1792
	s_waitcnt lgkmcnt(6)
	v_mfma_f32_32x32x16_bf16 v[16:31], v[228:231], v[224:227], v[16:31]
	s_waitcnt vmcnt(15)
	ds_write_b128 v177, v[76:79] offset:9216
	global_load_dwordx4 v[72:75], v[156:157], off offset:1792
	v_mfma_f32_32x32x16_bf16 v[0:15], v[228:231], v[220:223], v[0:15]
	s_waitcnt vmcnt(15)
	ds_write_b128 v177, v[80:83] offset:13824
	global_load_dwordx4 v[76:79], v[158:159], off offset:1792
	s_waitcnt lgkmcnt(6)
	v_mfma_f32_32x32x16_bf16 v[48:63], v[244:247], v[212:215], v[48:63]
	s_waitcnt vmcnt(15)
	ds_write_b128 v177, v[114:117] offset:36864
	global_load_dwordx4 v[80:83], v[150:151], off offset:1792
	s_waitcnt lgkmcnt(6)
	v_mfma_f32_32x32x16_bf16 v[32:47], v[244:247], v[252:255], v[32:47]
	s_waitcnt vmcnt(15)
	ds_write_b128 v177, v[122:125] offset:41472
	global_load_dwordx4 v[84:87], v[160:161], off offset:1792
	s_waitcnt lgkmcnt(5)
	v_mfma_f32_32x32x16_bf16 v[16:31], v[216:219], v[212:215], v[16:31]
	s_waitcnt vmcnt(15)
	ds_write_b128 v177, v[126:129] offset:46080
	global_load_dwordx4 v[88:91], v[170:171], off offset:1792
	v_mfma_f32_32x32x16_bf16 v[0:15], v[216:219], v[252:255], v[0:15]
	s_waitcnt vmcnt(15)
	ds_write_b128 v177, v[134:137] offset:50688
	global_load_dwordx4 v[92:95], v[172:173], off offset:1792
	s_setprio 0
	s_waitcnt lgkmcnt(0)
	s_barrier
	s_setprio 1
	ds_read_b128 v[212:215], v96 offset:36864
	ds_read_b128 v[216:219], v178
	ds_read_b128 v[220:223], v178 offset:4608
	ds_read_b128 v[224:227], v96 offset:41472
	ds_read_b128 v[228:231], v96 offset:36896
	ds_read_b128 v[244:247], v178 offset:32
	ds_read_b128 v[252:255], v178 offset:4640
	s_waitcnt lgkmcnt(5)
	v_mfma_f32_32x32x16_bf16 v[48:63], v[212:215], v[216:219], v[48:63]
	s_waitcnt lgkmcnt(4)
	v_mfma_f32_32x32x16_bf16 v[32:47], v[212:215], v[220:223], v[32:47]
	ds_read_b128 v[212:215], v96 offset:41504
	s_waitcnt lgkmcnt(4)
	v_mfma_f32_32x32x16_bf16 v[16:31], v[224:227], v[216:219], v[16:31]
	ds_read_b128 v[216:219], v96 offset:36928
	v_mfma_f32_32x32x16_bf16 v[0:15], v[224:227], v[220:223], v[0:15]
	ds_read_b128 v[224:227], v178 offset:64
	ds_read_b128 v[220:223], v178 offset:4672
	s_waitcnt lgkmcnt(5)
	v_mfma_f32_32x32x16_bf16 v[48:63], v[228:231], v[244:247], v[48:63]
	s_waitcnt lgkmcnt(4)
	v_mfma_f32_32x32x16_bf16 v[32:47], v[228:231], v[252:255], v[32:47]
	ds_read_b128 v[228:231], v96 offset:41536
	s_waitcnt lgkmcnt(4)
	v_mfma_f32_32x32x16_bf16 v[16:31], v[212:215], v[244:247], v[16:31]
	ds_read_b128 v[244:247], v96 offset:36960
	v_mfma_f32_32x32x16_bf16 v[0:15], v[212:215], v[252:255], v[0:15]
	ds_read_b128 v[212:215], v178 offset:96
	ds_read_b128 v[252:255], v178 offset:4704
	s_waitcnt lgkmcnt(5)
	v_mfma_f32_32x32x16_bf16 v[48:63], v[216:219], v[224:227], v[48:63]
	s_waitcnt vmcnt(15)
	ds_write_b128 v177, v[98:101] offset:18432
	s_waitcnt vmcnt(14)
	ds_write_b128 v177, v[102:105] offset:23040
	s_waitcnt lgkmcnt(6)
	v_mfma_f32_32x32x16_bf16 v[32:47], v[216:219], v[220:223], v[32:47]
	ds_read_b128 v[216:219], v96 offset:41568
	global_load_dwordx4 v[100:103], v[152:153], off offset:1920
	s_waitcnt vmcnt(14)
	ds_write_b128 v177, v[106:109] offset:27648
	s_waitcnt lgkmcnt(7)
	v_mfma_f32_32x32x16_bf16 v[16:31], v[228:231], v[224:227], v[16:31]
	global_load_dwordx4 v[104:107], v[154:155], off offset:1920
	s_waitcnt vmcnt(14)
	ds_write_b128 v177, v[110:113] offset:32256
	v_mfma_f32_32x32x16_bf16 v[0:15], v[228:231], v[220:223], v[0:15]
	global_load_dwordx4 v[108:111], v[156:157], off offset:1920
	global_load_dwordx4 v[112:115], v[158:159], off offset:1920
	s_waitcnt lgkmcnt(6)
	v_mfma_f32_32x32x16_bf16 v[48:63], v[244:247], v[212:215], v[48:63]
	s_waitcnt vmcnt(15)
	ds_write_b128 v177, v[118:121] offset:55296
	global_load_dwordx4 v[116:119], v[150:151], off offset:1920
	s_waitcnt lgkmcnt(6)
	v_mfma_f32_32x32x16_bf16 v[32:47], v[244:247], v[252:255], v[32:47]
	s_waitcnt vmcnt(15)
	ds_write_b128 v177, v[130:133] offset:59904
	global_load_dwordx4 v[120:123], v[160:161], off offset:1920
	s_waitcnt lgkmcnt(4)
	v_mfma_f32_32x32x16_bf16 v[16:31], v[216:219], v[212:215], v[16:31]
	s_waitcnt vmcnt(15)
	ds_write_b128 v177, v[138:141] offset:64512
	global_load_dwordx4 v[128:131], v[170:171], off offset:1920
	v_mfma_f32_32x32x16_bf16 v[0:15], v[216:219], v[252:255], v[0:15]
	s_waitcnt vmcnt(15)
	ds_write_b128 v179, v[142:145] offset:13824
	global_load_dwordx4 v[124:127], v[172:173], off offset:1920
	s_setprio 0
	s_waitcnt lgkmcnt(0)
	s_barrier
	s_setprio 1
	ds_read_b128 v[212:215], v96 offset:55296
	ds_read_b128 v[216:219], v178 offset:18432
	ds_read_b128 v[220:223], v178 offset:23040
	ds_read_b128 v[224:227], v96 offset:59904
	ds_read_b128 v[228:231], v96 offset:55328
	ds_read_b128 v[244:247], v178 offset:18464
	ds_read_b128 v[252:255], v178 offset:23072
	s_waitcnt lgkmcnt(5)
	v_mfma_f32_32x32x16_bf16 v[48:63], v[212:215], v[216:219], v[48:63]
	s_waitcnt lgkmcnt(4)
	v_mfma_f32_32x32x16_bf16 v[32:47], v[212:215], v[220:223], v[32:47]
	ds_read_b128 v[212:215], v96 offset:59936
	s_waitcnt lgkmcnt(4)
	v_mfma_f32_32x32x16_bf16 v[16:31], v[224:227], v[216:219], v[16:31]
	ds_read_b128 v[216:219], v96 offset:55360
	v_mfma_f32_32x32x16_bf16 v[0:15], v[224:227], v[220:223], v[0:15]
	ds_read_b128 v[224:227], v178 offset:18496
	ds_read_b128 v[220:223], v178 offset:23104
	s_waitcnt lgkmcnt(5)
	v_mfma_f32_32x32x16_bf16 v[48:63], v[228:231], v[244:247], v[48:63]
	s_waitcnt lgkmcnt(4)
	v_mfma_f32_32x32x16_bf16 v[32:47], v[228:231], v[252:255], v[32:47]
	ds_read_b128 v[228:231], v96 offset:59968
	s_waitcnt lgkmcnt(4)
	v_mfma_f32_32x32x16_bf16 v[16:31], v[212:215], v[244:247], v[16:31]
	ds_read_b128 v[244:247], v96 offset:55392
	v_mfma_f32_32x32x16_bf16 v[0:15], v[212:215], v[252:255], v[0:15]
	ds_read_b128 v[212:215], v178 offset:18528
	ds_read_b128 v[252:255], v178 offset:23136
	s_waitcnt lgkmcnt(5)
	v_mfma_f32_32x32x16_bf16 v[48:63], v[216:219], v[224:227], v[48:63]
	s_waitcnt lgkmcnt(4)
	v_mfma_f32_32x32x16_bf16 v[32:47], v[216:219], v[220:223], v[32:47]
	ds_read_b128 v[216:219], v96 offset:60000
	s_waitcnt lgkmcnt(4)
	v_mfma_f32_32x32x16_bf16 v[16:31], v[228:231], v[224:227], v[16:31]
	v_mfma_f32_32x32x16_bf16 v[0:15], v[228:231], v[220:223], v[0:15]
	s_waitcnt lgkmcnt(2)
	v_mfma_f32_32x32x16_bf16 v[48:63], v[244:247], v[212:215], v[48:63]
	s_waitcnt lgkmcnt(1)
	v_mfma_f32_32x32x16_bf16 v[32:47], v[244:247], v[252:255], v[32:47]
	s_waitcnt lgkmcnt(0)
	v_mfma_f32_32x32x16_bf16 v[16:31], v[216:219], v[212:215], v[16:31]
	v_mfma_f32_32x32x16_bf16 v[0:15], v[216:219], v[252:255], v[0:15]
	s_setprio 0
	v_cndmask_b32_e64 v98, 0, 1, s[12:13]
	v_cmp_ne_u32_e64 s[40:41], 1, v98
	s_andn2_b64 vcc, exec, s[12:13]
	s_waitcnt vmcnt(15)
	ds_write_b128 v177, v[64:67]
	s_waitcnt vmcnt(14)
	ds_write_b128 v177, v[68:71] offset:4608
	s_waitcnt vmcnt(13)
	ds_write_b128 v177, v[72:75] offset:9216
	s_waitcnt vmcnt(12)
	ds_write_b128 v177, v[76:79] offset:13824
	s_waitcnt vmcnt(11)
	ds_write_b128 v177, v[80:83] offset:36864
	s_waitcnt vmcnt(10)
	ds_write_b128 v177, v[84:87] offset:41472
	s_waitcnt vmcnt(9)
	ds_write_b128 v177, v[88:91] offset:46080
	s_waitcnt vmcnt(8)
	ds_write_b128 v177, v[92:95] offset:50688
	s_cbranch_vccnz .LBB0_474
	v_add_co_u32_e32 v68, vcc, 0x10000, v148
	global_load_dwordx4 v[64:67], v[148:149], off
	s_nop 0
	v_addc_co_u32_e32 v69, vcc, 0, v149, vcc
	v_add_co_u32_e32 v72, vcc, 0x20000, v148
	s_nop 1
	v_addc_co_u32_e32 v73, vcc, 0, v149, vcc
	v_add_co_u32_e32 v76, vcc, 0x30000, v148
	global_load_dwordx4 v[68:71], v[68:69], off
	global_load_dwordx4 v[72:75], v[72:73], off
	v_addc_co_u32_e32 v77, vcc, 0, v149, vcc
	v_add_co_u32_e32 v84, vcc, 0x10000, v146
	global_load_dwordx4 v[76:79], v[76:77], off
	s_nop 0
	global_load_dwordx4 v[80:83], v[146:147], off
	v_addc_co_u32_e32 v85, vcc, 0, v147, vcc
	v_add_co_u32_e32 v88, vcc, 0x20000, v146
	s_nop 1
	v_addc_co_u32_e32 v89, vcc, 0, v147, vcc
	v_add_co_u32_e32 v92, vcc, 0x30000, v146
	global_load_dwordx4 v[84:87], v[84:85], off
	s_nop 0
	global_load_dwordx4 v[88:91], v[88:89], off
	v_addc_co_u32_e32 v93, vcc, 0, v147, vcc
	global_load_dwordx4 v[92:95], v[92:93], off
.LBB0_474:
	s_waitcnt lgkmcnt(0)
	s_barrier
	s_setprio 1
	ds_read_b128 v[212:215], v96 offset:36864
	ds_read_b128 v[216:219], v178
	ds_read_b128 v[220:223], v178 offset:4608
	ds_read_b128 v[224:227], v96 offset:41472
	ds_read_b128 v[228:231], v96 offset:36896
	ds_read_b128 v[244:247], v178 offset:32
	ds_read_b128 v[252:255], v178 offset:4640
	s_waitcnt lgkmcnt(5)
	v_mfma_f32_32x32x16_bf16 v[48:63], v[212:215], v[216:219], v[48:63]
	s_waitcnt lgkmcnt(4)
	v_mfma_f32_32x32x16_bf16 v[32:47], v[212:215], v[220:223], v[32:47]
	ds_read_b128 v[212:215], v96 offset:41504
	s_waitcnt lgkmcnt(4)
	v_mfma_f32_32x32x16_bf16 v[16:31], v[224:227], v[216:219], v[16:31]
	ds_read_b128 v[216:219], v96 offset:36928
	v_mfma_f32_32x32x16_bf16 v[0:15], v[224:227], v[220:223], v[0:15]
	ds_read_b128 v[224:227], v178 offset:64
	ds_read_b128 v[220:223], v178 offset:4672
	s_waitcnt lgkmcnt(5)
	v_mfma_f32_32x32x16_bf16 v[48:63], v[228:231], v[244:247], v[48:63]
	s_waitcnt lgkmcnt(4)
	v_mfma_f32_32x32x16_bf16 v[32:47], v[228:231], v[252:255], v[32:47]
	ds_read_b128 v[228:231], v96 offset:41536
	s_waitcnt lgkmcnt(4)
	v_mfma_f32_32x32x16_bf16 v[16:31], v[212:215], v[244:247], v[16:31]
	ds_read_b128 v[244:247], v96 offset:36960
	v_mfma_f32_32x32x16_bf16 v[0:15], v[212:215], v[252:255], v[0:15]
	ds_read_b128 v[212:215], v178 offset:96
	ds_read_b128 v[252:255], v178 offset:4704
	s_waitcnt lgkmcnt(5)
	v_mfma_f32_32x32x16_bf16 v[48:63], v[216:219], v[224:227], v[48:63]
	s_waitcnt lgkmcnt(4)
	v_mfma_f32_32x32x16_bf16 v[32:47], v[216:219], v[220:223], v[32:47]
	ds_read_b128 v[216:219], v96 offset:41568
	s_waitcnt lgkmcnt(4)
	v_mfma_f32_32x32x16_bf16 v[16:31], v[228:231], v[224:227], v[16:31]
	v_mfma_f32_32x32x16_bf16 v[0:15], v[228:231], v[220:223], v[0:15]
	s_waitcnt lgkmcnt(2)
	v_mfma_f32_32x32x16_bf16 v[48:63], v[244:247], v[212:215], v[48:63]
	s_waitcnt lgkmcnt(1)
	v_mfma_f32_32x32x16_bf16 v[32:47], v[244:247], v[252:255], v[32:47]
	s_waitcnt lgkmcnt(0)
	v_mfma_f32_32x32x16_bf16 v[16:31], v[216:219], v[212:215], v[16:31]
	v_mfma_f32_32x32x16_bf16 v[0:15], v[216:219], v[252:255], v[0:15]
	s_setprio 0
	v_readlane_b32 s14, v248, 4
	s_and_b64 vcc, exec, s[40:41]
	v_readlane_b32 s15, v248, 5
	s_waitcnt vmcnt(7)
	ds_write_b128 v177, v[100:103] offset:18432
	s_waitcnt vmcnt(6)
	ds_write_b128 v177, v[104:107] offset:23040
	s_waitcnt vmcnt(5)
	ds_write_b128 v177, v[108:111] offset:27648
	s_waitcnt vmcnt(4)
	ds_write_b128 v177, v[112:115] offset:32256
	s_waitcnt vmcnt(3)
	ds_write_b128 v177, v[116:119] offset:55296
	s_waitcnt vmcnt(2)
	ds_write_b128 v177, v[120:123] offset:59904
	s_waitcnt vmcnt(1)
	ds_write_b128 v177, v[128:131] offset:64512
	s_waitcnt vmcnt(0)
	ds_write_b128 v179, v[124:127] offset:13824
	s_cbranch_vccnz .LBB0_476
	v_add_co_u32_e32 v98, vcc, 0x10000, v148
	global_load_dwordx4 v[100:103], v[148:149], off offset:128
	s_nop 0
	v_addc_co_u32_e32 v99, vcc, 0, v149, vcc
	v_add_co_u32_e32 v108, vcc, 0x20000, v148
	s_nop 1
	v_addc_co_u32_e32 v109, vcc, 0, v149, vcc
	global_load_dwordx4 v[104:107], v[98:99], off offset:128
	global_load_dwordx4 v[108:111], v[108:109], off offset:128
	v_add_co_u32_e32 v98, vcc, 0x30000, v148
	s_nop 1
	v_addc_co_u32_e32 v99, vcc, 0, v149, vcc
	global_load_dwordx4 v[112:115], v[98:99], off offset:128
	global_load_dwordx4 v[116:119], v[146:147], off offset:128
	v_add_co_u32_e32 v98, vcc, 0x10000, v146
	s_nop 1
	v_addc_co_u32_e32 v99, vcc, 0, v147, vcc
	v_add_co_u32_e32 v124, vcc, 0x20000, v146
	s_nop 1
	v_addc_co_u32_e32 v125, vcc, 0, v147, vcc
	global_load_dwordx4 v[120:123], v[98:99], off offset:128
	global_load_dwordx4 v[128:131], v[124:125], off offset:128
	v_add_co_u32_e32 v98, vcc, 0x30000, v146
	s_nop 1
	v_addc_co_u32_e32 v99, vcc, 0, v147, vcc
	global_load_dwordx4 v[124:127], v[98:99], off offset:128
.LBB0_476:
	s_waitcnt lgkmcnt(0)
	s_barrier
	s_setprio 1
	ds_read_b128 v[212:215], v96 offset:55296
	ds_read_b128 v[216:219], v178 offset:18432
	ds_read_b128 v[220:223], v178 offset:23040
	ds_read_b128 v[224:227], v96 offset:59904
	ds_read_b128 v[228:231], v96 offset:55328
	ds_read_b128 v[244:247], v178 offset:18464
	ds_read_b128 v[252:255], v178 offset:23072
	s_waitcnt lgkmcnt(5)
	v_mfma_f32_32x32x16_bf16 v[48:63], v[212:215], v[216:219], v[48:63]
	s_waitcnt lgkmcnt(4)
	v_mfma_f32_32x32x16_bf16 v[32:47], v[212:215], v[220:223], v[32:47]
	ds_read_b128 v[212:215], v96 offset:59936
	s_waitcnt lgkmcnt(4)
	v_mfma_f32_32x32x16_bf16 v[16:31], v[224:227], v[216:219], v[16:31]
	ds_read_b128 v[216:219], v96 offset:55360
	v_mfma_f32_32x32x16_bf16 v[0:15], v[224:227], v[220:223], v[0:15]
	ds_read_b128 v[224:227], v178 offset:18496
	ds_read_b128 v[220:223], v178 offset:23104
	s_waitcnt lgkmcnt(5)
	v_mfma_f32_32x32x16_bf16 v[48:63], v[228:231], v[244:247], v[48:63]
	s_waitcnt lgkmcnt(4)
	v_mfma_f32_32x32x16_bf16 v[32:47], v[228:231], v[252:255], v[32:47]
	ds_read_b128 v[228:231], v96 offset:59968
	s_waitcnt lgkmcnt(4)
	v_mfma_f32_32x32x16_bf16 v[16:31], v[212:215], v[244:247], v[16:31]
	ds_read_b128 v[244:247], v96 offset:55392
	v_mfma_f32_32x32x16_bf16 v[0:15], v[212:215], v[252:255], v[0:15]
	ds_read_b128 v[212:215], v178 offset:18528
	ds_read_b128 v[252:255], v178 offset:23136
	s_waitcnt lgkmcnt(5)
	v_mfma_f32_32x32x16_bf16 v[48:63], v[216:219], v[224:227], v[48:63]
	s_waitcnt lgkmcnt(4)
	v_mfma_f32_32x32x16_bf16 v[32:47], v[216:219], v[220:223], v[32:47]
	ds_read_b128 v[216:219], v96 offset:60000
	s_waitcnt lgkmcnt(4)
	v_mfma_f32_32x32x16_bf16 v[16:31], v[228:231], v[224:227], v[16:31]
	v_mfma_f32_32x32x16_bf16 v[0:15], v[228:231], v[220:223], v[0:15]
	s_waitcnt lgkmcnt(2)
	v_mfma_f32_32x32x16_bf16 v[48:63], v[244:247], v[212:215], v[48:63]
	s_waitcnt lgkmcnt(1)
	v_mfma_f32_32x32x16_bf16 v[32:47], v[244:247], v[252:255], v[32:47]
	s_waitcnt lgkmcnt(0)
	v_mfma_f32_32x32x16_bf16 v[16:31], v[216:219], v[212:215], v[16:31]
	v_mfma_f32_32x32x16_bf16 v[0:15], v[216:219], v[252:255], v[0:15]
	s_setprio 0
	s_and_b64 vcc, exec, s[40:41]
	s_cbranch_vccnz .LBB0_478
	ds_write_b128 v177, v[64:67]
	ds_write_b128 v177, v[68:71] offset:4608
	ds_write_b128 v177, v[72:75] offset:9216
	ds_write_b128 v177, v[76:79] offset:13824
	ds_write_b128 v177, v[80:83] offset:36864
	ds_write_b128 v177, v[84:87] offset:41472
	ds_write_b128 v177, v[88:91] offset:46080
	ds_write_b128 v177, v[92:95] offset:50688
	v_add_co_u32_e32 v68, vcc, 0x10000, v148
	global_load_dwordx4 v[64:67], v[148:149], off offset:256
	s_nop 0
	v_addc_co_u32_e32 v69, vcc, 0, v149, vcc
	v_add_co_u32_e32 v72, vcc, 0x20000, v148
	s_nop 1
	v_addc_co_u32_e32 v73, vcc, 0, v149, vcc
	v_add_co_u32_e32 v76, vcc, 0x30000, v148
	global_load_dwordx4 v[68:71], v[68:69], off offset:256
	s_nop 0
	global_load_dwordx4 v[72:75], v[72:73], off offset:256
	v_addc_co_u32_e32 v77, vcc, 0, v149, vcc
	v_add_co_u32_e32 v84, vcc, 0x10000, v146
	global_load_dwordx4 v[76:79], v[76:77], off offset:256
	global_load_dwordx4 v[80:83], v[146:147], off offset:256
	v_addc_co_u32_e32 v85, vcc, 0, v147, vcc
	v_add_co_u32_e32 v88, vcc, 0x20000, v146
	s_nop 1
	v_addc_co_u32_e32 v89, vcc, 0, v147, vcc
	v_add_co_u32_e32 v92, vcc, 0x30000, v146
	global_load_dwordx4 v[84:87], v[84:85], off offset:256
	global_load_dwordx4 v[88:91], v[88:89], off offset:256
	v_addc_co_u32_e32 v93, vcc, 0, v147, vcc
	global_load_dwordx4 v[92:95], v[92:93], off offset:256

.LBB0_483:
	v_mbcnt_hi_u32_b32 v98, -1, v195
	v_and_b32_e32 v132, 64, v98
	v_xor_b32_e32 v99, 32, v98
	v_add_u32_e32 v132, 64, v132
	v_cmp_lt_i32_e32 vcc, v99, v132
	v_cvt_pk_bf16_f32 v48, v48, v49
	v_cvt_pk_bf16_f32 v49, v50, v51
	v_cndmask_b32_e32 v98, v98, v99, vcc
	v_cvt_pk_bf16_f32 v51, v54, v55
	v_cvt_pk_bf16_f32 v32, v32, v33
	v_cvt_pk_bf16_f32 v33, v34, v35
	v_cvt_pk_bf16_f32 v34, v36, v37
	v_lshlrev_b32_e32 v132, 2, v98
	v_cvt_pk_bf16_f32 v50, v52, v53
	v_cndmask_b32_e64 v53, v49, v51, s[38:39]
	v_cndmask_b32_e64 v36, v32, v34, s[38:39]
	v_mov_b32_e32 v133, v53
	v_mov_b32_e32 v255, v53
	s_nop 1
	v_permlane32_swap_b32_e32 v133, v255
	s_nop 1
	v_mov_b32_dpp v133, v255 quad_perm:[0,1,2,3] row_mask:0x3 bank_mask:0xf
	v_cvt_pk_bf16_f32 v35, v38, v39
	v_mov_b32_e32 v38, v36
	v_mov_b32_e32 v255, v36
	s_nop 1
	v_permlane32_swap_b32_e32 v38, v255
	s_nop 1
	v_mov_b32_dpp v38, v255 quad_perm:[0,1,2,3] row_mask:0x3 bank_mask:0xf
	v_cndmask_b32_e64 v52, v48, v50, s[38:39]
	v_mov_b32_e32 v99, v52
	v_mov_b32_e32 v255, v52
	s_nop 1
	v_permlane32_swap_b32_e32 v99, v255
	s_nop 1
	v_mov_b32_dpp v99, v255 quad_perm:[0,1,2,3] row_mask:0x3 bank_mask:0xf
	v_cvt_pk_bf16_f32 v16, v16, v17
	v_cvt_pk_bf16_f32 v17, v18, v19
	v_cvt_pk_bf16_f32 v18, v20, v21
	v_cvt_pk_bf16_f32 v19, v22, v23
	v_cvt_pk_bf16_f32 v0, v0, v1
	v_cvt_pk_bf16_f32 v1, v2, v3
	v_cvt_pk_bf16_f32 v2, v4, v5
	v_cvt_pk_bf16_f32 v3, v6, v7
	s_waitcnt lgkmcnt(0)
	v_cndmask_b32_e64 v49, v133, v49, s[38:39]
	v_cndmask_b32_e64 v51, v51, v133, s[38:39]
	v_cvt_pk_bf16_f32 v133, v56, v57
	v_cvt_pk_bf16_f32 v58, v58, v59
	v_cvt_pk_bf16_f32 v59, v60, v61
	v_cvt_pk_bf16_f32 v60, v62, v63
	v_cndmask_b32_e64 v37, v33, v35, s[38:39]
	v_cndmask_b32_e64 v32, v38, v32, s[38:39]
	v_cndmask_b32_e64 v34, v34, v38, s[38:39]
	v_cvt_pk_bf16_f32 v38, v40, v41
	v_cvt_pk_bf16_f32 v40, v42, v43
	v_cvt_pk_bf16_f32 v41, v44, v45
	v_cvt_pk_bf16_f32 v42, v46, v47
	v_cndmask_b32_e64 v20, v16, v18, s[38:39]
	v_cndmask_b32_e64 v21, v17, v19, s[38:39]
	v_cvt_pk_bf16_f32 v22, v24, v25
	v_cvt_pk_bf16_f32 v23, v26, v27
	v_cvt_pk_bf16_f32 v24, v28, v29
	v_cvt_pk_bf16_f32 v25, v30, v31
	v_cndmask_b32_e64 v4, v0, v2, s[38:39]
	v_cndmask_b32_e64 v5, v1, v3, s[38:39]
	v_cvt_pk_bf16_f32 v6, v8, v9
	v_cvt_pk_bf16_f32 v7, v10, v11
	v_cvt_pk_bf16_f32 v8, v12, v13
	v_cvt_pk_bf16_f32 v9, v14, v15
	v_cndmask_b32_e64 v56, v133, v59, s[38:39]
	v_cndmask_b32_e64 v57, v58, v60, s[38:39]
	v_mov_b32_e32 v39, v37
	v_mov_b32_e32 v255, v37
	s_nop 1
	v_permlane32_swap_b32_e32 v39, v255
	s_nop 1
	v_mov_b32_dpp v39, v255 quad_perm:[0,1,2,3] row_mask:0x3 bank_mask:0xf
	v_cndmask_b32_e64 v43, v38, v41, s[38:39]
	v_cndmask_b32_e64 v44, v40, v42, s[38:39]
	v_mov_b32_e32 v255, v20
	s_nop 1
	v_permlane32_swap_b32_e32 v20, v255
	s_nop 1
	v_mov_b32_dpp v20, v255 quad_perm:[0,1,2,3] row_mask:0x3 bank_mask:0xf
	v_mov_b32_e32 v255, v21
	s_nop 1
	v_permlane32_swap_b32_e32 v21, v255
	s_nop 1
	v_mov_b32_dpp v21, v255 quad_perm:[0,1,2,3] row_mask:0x3 bank_mask:0xf
	v_cndmask_b32_e64 v26, v22, v24, s[38:39]
	v_cndmask_b32_e64 v27, v23, v25, s[38:39]
	v_mov_b32_e32 v255, v4
	s_nop 1
	v_permlane32_swap_b32_e32 v4, v255
	s_nop 1
	v_mov_b32_dpp v4, v255 quad_perm:[0,1,2,3] row_mask:0x3 bank_mask:0xf
	v_mov_b32_e32 v255, v5
	s_nop 1
	v_permlane32_swap_b32_e32 v5, v255
	s_nop 1
	v_mov_b32_dpp v5, v255 quad_perm:[0,1,2,3] row_mask:0x3 bank_mask:0xf
	v_cndmask_b32_e64 v10, v6, v8, s[38:39]
	v_cndmask_b32_e64 v11, v7, v9, s[38:39]
	v_lshl_or_b32 v98, s2, 7, v176
	v_readlane_b32 s2, v249, 7
	v_mov_b32_e32 v61, v56
	v_mov_b32_e32 v255, v56
	s_nop 1
	v_permlane32_swap_b32_e32 v61, v255
	s_nop 1
	v_mov_b32_dpp v61, v255 quad_perm:[0,1,2,3] row_mask:0x3 bank_mask:0xf
	v_mov_b32_e32 v62, v57
	v_mov_b32_e32 v255, v57
	s_nop 1
	v_permlane32_swap_b32_e32 v62, v255
	s_nop 1
	v_mov_b32_dpp v62, v255 quad_perm:[0,1,2,3] row_mask:0x3 bank_mask:0xf
	v_mov_b32_e32 v255, v43
	s_nop 1
	v_permlane32_swap_b32_e32 v43, v255
	s_nop 1
	v_mov_b32_dpp v43, v255 quad_perm:[0,1,2,3] row_mask:0x3 bank_mask:0xf
	v_mov_b32_e32 v255, v44
	s_nop 1
	v_permlane32_swap_b32_e32 v44, v255
	s_nop 1
	v_mov_b32_dpp v44, v255 quad_perm:[0,1,2,3] row_mask:0x3 bank_mask:0xf
	v_mov_b32_e32 v255, v26
	s_nop 1
	v_permlane32_swap_b32_e32 v26, v255
	s_nop 1
	v_mov_b32_dpp v26, v255 quad_perm:[0,1,2,3] row_mask:0x3 bank_mask:0xf
	v_mov_b32_e32 v255, v27
	s_nop 1
	v_permlane32_swap_b32_e32 v27, v255
	s_nop 1
	v_mov_b32_dpp v27, v255 quad_perm:[0,1,2,3] row_mask:0x3 bank_mask:0xf
	v_mov_b32_e32 v255, v10
	s_nop 1
	v_permlane32_swap_b32_e32 v10, v255
	s_nop 1
	v_mov_b32_dpp v10, v255 quad_perm:[0,1,2,3] row_mask:0x3 bank_mask:0xf
	v_mov_b32_e32 v255, v11
	s_nop 1
	v_permlane32_swap_b32_e32 v11, v255
	s_nop 1
	v_mov_b32_dpp v11, v255 quad_perm:[0,1,2,3] row_mask:0x3 bank_mask:0xf
	v_lshl_add_u32 v96, s6, 7, v175
	v_readlane_b32 s3, v249, 8
	v_cndmask_b32_e64 v48, v99, v48, s[38:39]
	v_cndmask_b32_e64 v50, v50, v99, s[38:39]
	v_mov_b64_e32 v[52:53], s[2:3]
	v_ashrrev_i32_e32 v99, 31, v98
	v_or_b32_e32 v36, 32, v96
	v_mad_i64_i32 v[54:55], s[2:3], v96, s74, v[52:53]
	v_lshlrev_b64 v[56:57], 1, v[98:99]
	v_mad_i64_i32 v[36:37], s[2:3], v36, s74, v[52:53]
	v_lshl_add_u64 v[54:55], v[54:55], 0, v[56:57]
	v_cndmask_b32_e64 v33, v39, v33, s[38:39]
	v_cndmask_b32_e64 v35, v35, v39, s[38:39]
	v_lshl_add_u64 v[36:37], v[36:37], 0, v[56:57]
	v_cndmask_b32_e64 v16, v20, v16, s[38:39]
	v_cndmask_b32_e64 v17, v21, v17, s[38:39]
	v_cndmask_b32_e64 v18, v18, v20, s[38:39]
	v_cndmask_b32_e64 v19, v19, v21, s[38:39]
	v_cndmask_b32_e64 v0, v4, v0, s[38:39]
	v_cndmask_b32_e64 v1, v5, v1, s[38:39]
	v_cndmask_b32_e64 v2, v2, v4, s[38:39]
	v_cndmask_b32_e64 v3, v3, v5, s[38:39]
	global_store_dwordx4 v[54:55], v[48:51], off
	global_store_dwordx4 v[36:37], v[32:35], off
	global_store_dwordx4 v[54:55], v[16:19], off offset:64
	v_cndmask_b32_e64 v48, v61, v133, s[38:39]
	v_cndmask_b32_e64 v49, v62, v58, s[38:39]
	v_cndmask_b32_e64 v50, v59, v61, s[38:39]
	v_cndmask_b32_e64 v51, v60, v62, s[38:39]
	v_cndmask_b32_e64 v32, v43, v38, s[38:39]
	v_cndmask_b32_e64 v33, v44, v40, s[38:39]
	v_cndmask_b32_e64 v34, v41, v43, s[38:39]
	v_cndmask_b32_e64 v35, v42, v44, s[38:39]
	v_cndmask_b32_e64 v16, v26, v22, s[38:39]
	v_cndmask_b32_e64 v17, v27, v23, s[38:39]
	v_cndmask_b32_e64 v18, v24, v26, s[38:39]
	v_cndmask_b32_e64 v19, v25, v27, s[38:39]
	global_store_dwordx4 v[36:37], v[0:3], off offset:64
	global_store_dwordx4 v[54:55], v[48:51], off offset:32
	global_store_dwordx4 v[36:37], v[32:35], off offset:32
	v_cndmask_b32_e64 v0, v10, v6, s[38:39]
	v_cndmask_b32_e64 v1, v11, v7, s[38:39]
	v_cndmask_b32_e64 v2, v8, v10, s[38:39]
	v_cndmask_b32_e64 v3, v9, v11, s[38:39]
	global_store_dwordx4 v[54:55], v[16:19], off offset:96
	global_store_dwordx4 v[36:37], v[0:3], off offset:96
	s_branch .LBB0_442

.LBB0_540:
	s_or_b64 exec, exec, s[6:7]
	v_ashrrev_i32_e32 v9, 31, v8
	v_mad_i64_i32 v[6:7], s[0:1], v8, s74, v[0:1]
	v_lshlrev_b64 v[4:5], 8, v[8:9]
	v_lshlrev_b64 v[8:9], 10, v[8:9]
	v_lshl_add_u64 v[10:11], v[2:3], 0, v[8:9]
	global_load_ushort v8, v[6:7], off
	global_load_ushort v9, v[6:7], off offset:128
	global_load_ushort v78, v[6:7], off offset:256
	global_load_ushort v79, v[6:7], off offset:384
	global_load_ushort v80, v[6:7], off offset:512
	global_load_ushort v81, v[6:7], off offset:640
	global_load_ushort v82, v[6:7], off offset:768
	global_load_ushort v83, v[6:7], off offset:896
	global_load_ushort v84, v[6:7], off offset:1024
	global_load_ushort v85, v[6:7], off offset:1152
	s_mov_b32 s0, 0x358637bd
	v_lshl_add_u64 v[4:5], s[92:93], 0, v[4:5]
	v_lshl_add_u64 v[4:5], v[4:5], 0, v[96:97]
	s_mov_b32 s4, 0xc600000
	s_add_i32 s3, s3, 1
	s_cmp_lg_u32 s3, 8
	s_waitcnt vmcnt(9)
	v_lshlrev_b32_e32 v27, 16, v8
	s_waitcnt vmcnt(8)
	v_lshlrev_b32_e32 v26, 16, v9
	v_pk_mul_f32 v[8:9], v[26:27], v[26:27]
	v_mov_b32_e32 v255, v9
	s_nop 1
	v_permlane32_swap_b32_e32 v9, v255
	s_nop 1
	v_mov_b32_dpp v9, v255 quad_perm:[0,1,2,3] row_mask:0x3 bank_mask:0xf
	v_mov_b32_e32 v255, v8
	s_nop 1
	v_permlane32_swap_b32_e32 v8, v255
	s_nop 1
	v_mov_b32_dpp v8, v255 quad_perm:[0,1,2,3] row_mask:0x3 bank_mask:0xf
	s_waitcnt lgkmcnt(0)
	v_pk_fma_f32 v[8:9], v[26:27], v[26:27], v[8:9]
	v_mov_b32_e32 v29, v9
	v_mov_b32_e32 v255, v9
	s_nop 1
	v_permlane16_swap_b32_e32 v29, v255
	s_nop 1
	v_mov_b32_dpp v29, v255 quad_perm:[0,1,2,3] row_mask:0x5 bank_mask:0xf
	v_mov_b32_e32 v28, v8
	v_mov_b32_e32 v255, v8
	s_nop 1
	v_permlane16_swap_b32_e32 v28, v255
	s_nop 1
	v_mov_b32_dpp v28, v255 quad_perm:[0,1,2,3] row_mask:0x5 bank_mask:0xf
	v_pk_add_f32 v[8:9], v[8:9], v[28:29]
	s_nop 1
	v_mov_b32_dpp v29, v9 row_ror:8 row_mask:0xf bank_mask:0xf
	v_mov_b32_dpp v28, v8 row_ror:8 row_mask:0xf bank_mask:0xf
	v_pk_add_f32 v[8:9], v[8:9], v[28:29]
	s_nop 1
	v_mov_b32_dpp v29, v9 row_shl:4 row_mask:0xf bank_mask:0x5
	v_mov_b32_dpp v29, v9 row_shr:4 row_mask:0xf bank_mask:0xa
	v_mov_b32_dpp v28, v8 row_shl:4 row_mask:0xf bank_mask:0x5
	v_mov_b32_dpp v28, v8 row_shr:4 row_mask:0xf bank_mask:0xa
	v_pk_add_f32 v[8:9], v[8:9], v[28:29]
	s_nop 1
	v_mov_b32_dpp v29, v9 quad_perm:[2,3,0,1] row_mask:0xf bank_mask:0xf
	v_mov_b32_dpp v28, v8 quad_perm:[2,3,0,1] row_mask:0xf bank_mask:0xf
	v_pk_add_f32 v[8:9], v[8:9], v[28:29]
	s_nop 1
	v_mov_b32_dpp v29, v9 quad_perm:[1,0,3,2] row_mask:0xf bank_mask:0xf
	v_mov_b32_dpp v28, v8 quad_perm:[1,0,3,2] row_mask:0xf bank_mask:0xf
	v_pk_add_f32 v[28:29], v[8:9], v[28:29]
	v_mov_b64_e32 v[8:9], s[0:1]
	v_pk_fma_f32 v[28:29], v[28:29], s[10:11], v[8:9] op_sel_hi:[1,0,0]
	v_mul_f32_e32 v25, 0x4b800000, v29
	v_cmp_gt_f32_e64 s[40:41], s86, v29
	v_cmp_gt_f32_e64 s[0:1], s86, v28
	s_nop 0
	v_cndmask_b32_e64 v25, v29, v25, s[40:41]
	v_rsq_f32_e32 v25, v25
	s_nop 0
	v_mul_f32_e32 v29, 0x45800000, v25
	v_cndmask_b32_e64 v25, v25, v29, s[40:41]
	v_mul_f32_e32 v25, v25, v27
	v_mul_f32_e32 v25, v12, v25
	v_mov_b32_e32 v27, v25
	v_mov_b32_e32 v255, v25
	s_nop 1
	v_permlane16_swap_b32_e32 v27, v255
	s_nop 1
	v_mov_b32_dpp v27, v255 quad_perm:[0,1,2,3] row_mask:0x5 bank_mask:0xf
	v_mul_f32_e32 v25, v23, v25
	v_cndmask_b32_e64 v27, v27, -v27, vcc
	v_fmac_f32_e32 v25, v24, v27
	v_mul_f32_e32 v25, 0x3e000000, v25
	v_cvt_pk_bf16_f32 v25, v25, s0
	global_store_short v[10:11], v25, off
	v_mul_f32_e32 v25, 0x4b800000, v28
	v_cndmask_b32_e64 v25, v28, v25, s[0:1]
	v_rsq_f32_e32 v25, v25
	s_nop 0
	v_mul_f32_e32 v27, 0x45800000, v25
	v_cndmask_b32_e64 v25, v25, v27, s[0:1]
	v_mul_f32_e32 v25, v25, v26
	v_mul_f32_e32 v25, v12, v25
	v_mov_b32_e32 v26, v25
	v_mov_b32_e32 v255, v25
	s_nop 1
	v_permlane16_swap_b32_e32 v26, v255
	s_nop 1
	v_mov_b32_dpp v26, v255 quad_perm:[0,1,2,3] row_mask:0x5 bank_mask:0xf
	v_mul_f32_e32 v25, v23, v25
	v_cndmask_b32_e64 v26, v26, -v26, vcc
	v_fmac_f32_e32 v25, v24, v26
	v_mul_f32_e32 v25, 0x3e000000, v25
	v_cvt_pk_bf16_f32 v25, v25, s0
	global_store_short v[10:11], v25, off offset:128
	s_waitcnt vmcnt(9)
	v_mov_b32_e32 v25, v78
	v_lshlrev_b32_e32 v27, 16, v25
	s_waitcnt vmcnt(8)
	v_mov_b32_e32 v26, v79
	v_lshlrev_b32_e32 v26, 16, v26
	v_pk_mul_f32 v[28:29], v[26:27], v[26:27]
	v_mov_b32_e32 v255, v29
	s_nop 1
	v_permlane32_swap_b32_e32 v29, v255
	s_nop 1
	v_mov_b32_dpp v29, v255 quad_perm:[0,1,2,3] row_mask:0x3 bank_mask:0xf
	v_mov_b32_e32 v255, v28
	s_nop 1
	v_permlane32_swap_b32_e32 v28, v255
	s_nop 1
	v_mov_b32_dpp v28, v255 quad_perm:[0,1,2,3] row_mask:0x3 bank_mask:0xf
	v_pk_fma_f32 v[28:29], v[26:27], v[26:27], v[28:29]
	v_mov_b32_e32 v31, v29
	v_mov_b32_e32 v255, v29
	s_nop 1
	v_permlane16_swap_b32_e32 v31, v255
	s_nop 1
	v_mov_b32_dpp v31, v255 quad_perm:[0,1,2,3] row_mask:0x5 bank_mask:0xf
	v_mov_b32_e32 v30, v28
	v_mov_b32_e32 v255, v28
	s_nop 1
	v_permlane16_swap_b32_e32 v30, v255
	s_nop 1
	v_mov_b32_dpp v30, v255 quad_perm:[0,1,2,3] row_mask:0x5 bank_mask:0xf
	v_pk_add_f32 v[28:29], v[28:29], v[30:31]
	s_nop 1
	v_mov_b32_dpp v31, v29 row_ror:8 row_mask:0xf bank_mask:0xf
	v_mov_b32_dpp v30, v28 row_ror:8 row_mask:0xf bank_mask:0xf
	v_pk_add_f32 v[28:29], v[28:29], v[30:31]
	s_nop 1
	v_mov_b32_dpp v31, v29 row_shl:4 row_mask:0xf bank_mask:0x5
	v_mov_b32_dpp v31, v29 row_shr:4 row_mask:0xf bank_mask:0xa
	v_mov_b32_dpp v30, v28 row_shl:4 row_mask:0xf bank_mask:0x5
	v_mov_b32_dpp v30, v28 row_shr:4 row_mask:0xf bank_mask:0xa
	v_pk_add_f32 v[28:29], v[28:29], v[30:31]
	s_nop 1
	v_mov_b32_dpp v31, v29 quad_perm:[2,3,0,1] row_mask:0xf bank_mask:0xf
	v_mov_b32_dpp v30, v28 quad_perm:[2,3,0,1] row_mask:0xf bank_mask:0xf
	v_pk_add_f32 v[28:29], v[28:29], v[30:31]
	s_nop 1
	v_mov_b32_dpp v31, v29 quad_perm:[1,0,3,2] row_mask:0xf bank_mask:0xf
	v_mov_b32_dpp v30, v28 quad_perm:[1,0,3,2] row_mask:0xf bank_mask:0xf
	v_pk_add_f32 v[28:29], v[28:29], v[30:31]
	v_pk_fma_f32 v[28:29], v[28:29], s[10:11], v[8:9] op_sel_hi:[1,0,0]
	v_mul_f32_e32 v25, 0x4b800000, v29
	v_cmp_gt_f32_e64 s[40:41], s86, v29
	v_cmp_gt_f32_e64 s[0:1], s86, v28
	s_nop 0
	v_cndmask_b32_e64 v25, v29, v25, s[40:41]
	v_rsq_f32_e32 v25, v25
	s_nop 0
	v_mul_f32_e32 v29, 0x45800000, v25
	v_cndmask_b32_e64 v25, v25, v29, s[40:41]
	v_mul_f32_e32 v25, v25, v27
	v_mul_f32_e32 v25, v12, v25
	v_mov_b32_e32 v27, v25
	v_mov_b32_e32 v255, v25
	s_nop 1
	v_permlane16_swap_b32_e32 v27, v255
	s_nop 1
	v_mov_b32_dpp v27, v255 quad_perm:[0,1,2,3] row_mask:0x5 bank_mask:0xf
	v_mul_f32_e32 v25, v23, v25
	v_cndmask_b32_e64 v27, v27, -v27, vcc
	v_fmac_f32_e32 v25, v24, v27
	v_mul_f32_e32 v25, 0x3e000000, v25
	v_cvt_pk_bf16_f32 v25, v25, s0
	global_store_short v[10:11], v25, off offset:256
	v_mul_f32_e32 v25, 0x4b800000, v28
	v_cndmask_b32_e64 v25, v28, v25, s[0:1]
	v_rsq_f32_e32 v25, v25
	s_nop 0
	v_mul_f32_e32 v27, 0x45800000, v25
	v_cndmask_b32_e64 v25, v25, v27, s[0:1]
	v_mul_f32_e32 v25, v25, v26
	v_mul_f32_e32 v25, v12, v25
	v_mov_b32_e32 v26, v25
	v_mov_b32_e32 v255, v25
	s_nop 1
	v_permlane16_swap_b32_e32 v26, v255
	s_nop 1
	v_mov_b32_dpp v26, v255 quad_perm:[0,1,2,3] row_mask:0x5 bank_mask:0xf
	v_mul_f32_e32 v25, v23, v25
	v_cndmask_b32_e64 v26, v26, -v26, vcc
	v_fmac_f32_e32 v25, v24, v26
	v_mul_f32_e32 v25, 0x3e000000, v25
	v_cvt_pk_bf16_f32 v25, v25, s0
	global_store_short v[10:11], v25, off offset:384
	s_waitcnt vmcnt(9)
	v_mov_b32_e32 v25, v80
	v_lshlrev_b32_e32 v27, 16, v25
	s_waitcnt vmcnt(8)
	v_mov_b32_e32 v26, v81
	v_lshlrev_b32_e32 v26, 16, v26
	v_pk_mul_f32 v[28:29], v[26:27], v[26:27]
	v_mov_b32_e32 v255, v29
	s_nop 1
	v_permlane32_swap_b32_e32 v29, v255
	s_nop 1
	v_mov_b32_dpp v29, v255 quad_perm:[0,1,2,3] row_mask:0x3 bank_mask:0xf
	v_mov_b32_e32 v255, v28
	s_nop 1
	v_permlane32_swap_b32_e32 v28, v255
	s_nop 1
	v_mov_b32_dpp v28, v255 quad_perm:[0,1,2,3] row_mask:0x3 bank_mask:0xf
	v_pk_fma_f32 v[28:29], v[26:27], v[26:27], v[28:29]
	v_mov_b32_e32 v31, v29
	v_mov_b32_e32 v255, v29
	s_nop 1
	v_permlane16_swap_b32_e32 v31, v255
	s_nop 1
	v_mov_b32_dpp v31, v255 quad_perm:[0,1,2,3] row_mask:0x5 bank_mask:0xf
	v_mov_b32_e32 v30, v28
	v_mov_b32_e32 v255, v28
	s_nop 1
	v_permlane16_swap_b32_e32 v30, v255
	s_nop 1
	v_mov_b32_dpp v30, v255 quad_perm:[0,1,2,3] row_mask:0x5 bank_mask:0xf
	v_pk_add_f32 v[28:29], v[28:29], v[30:31]
	s_nop 1
	v_mov_b32_dpp v31, v29 row_ror:8 row_mask:0xf bank_mask:0xf
	v_mov_b32_dpp v30, v28 row_ror:8 row_mask:0xf bank_mask:0xf
	v_pk_add_f32 v[28:29], v[28:29], v[30:31]
	s_nop 1
	v_mov_b32_dpp v31, v29 row_shl:4 row_mask:0xf bank_mask:0x5
	v_mov_b32_dpp v31, v29 row_shr:4 row_mask:0xf bank_mask:0xa
	v_mov_b32_dpp v30, v28 row_shl:4 row_mask:0xf bank_mask:0x5
	v_mov_b32_dpp v30, v28 row_shr:4 row_mask:0xf bank_mask:0xa
	v_pk_add_f32 v[28:29], v[28:29], v[30:31]
	s_nop 1
	v_mov_b32_dpp v31, v29 quad_perm:[2,3,0,1] row_mask:0xf bank_mask:0xf
	v_mov_b32_dpp v30, v28 quad_perm:[2,3,0,1] row_mask:0xf bank_mask:0xf
	v_pk_add_f32 v[28:29], v[28:29], v[30:31]
	s_nop 1
	v_mov_b32_dpp v31, v29 quad_perm:[1,0,3,2] row_mask:0xf bank_mask:0xf
	v_mov_b32_dpp v30, v28 quad_perm:[1,0,3,2] row_mask:0xf bank_mask:0xf
	v_pk_add_f32 v[28:29], v[28:29], v[30:31]
	v_pk_fma_f32 v[28:29], v[28:29], s[10:11], v[8:9] op_sel_hi:[1,0,0]
	v_mul_f32_e32 v25, 0x4b800000, v29
	v_cmp_gt_f32_e64 s[40:41], s86, v29
	v_cmp_gt_f32_e64 s[0:1], s86, v28
	s_nop 0
	v_cndmask_b32_e64 v25, v29, v25, s[40:41]
	v_rsq_f32_e32 v25, v25
	s_nop 0
	v_mul_f32_e32 v29, 0x45800000, v25
	v_cndmask_b32_e64 v25, v25, v29, s[40:41]
	v_mul_f32_e32 v25, v25, v27
	v_mul_f32_e32 v25, v12, v25
	v_mov_b32_e32 v27, v25
	v_mov_b32_e32 v255, v25
	s_nop 1
	v_permlane16_swap_b32_e32 v27, v255
	s_nop 1
	v_mov_b32_dpp v27, v255 quad_perm:[0,1,2,3] row_mask:0x5 bank_mask:0xf
	v_mul_f32_e32 v25, v23, v25
	v_cndmask_b32_e64 v27, v27, -v27, vcc
	v_fmac_f32_e32 v25, v24, v27
	v_mul_f32_e32 v25, 0x3e000000, v25
	v_cvt_pk_bf16_f32 v25, v25, s0
	global_store_short v[10:11], v25, off offset:512
	v_mul_f32_e32 v25, 0x4b800000, v28
	v_cndmask_b32_e64 v25, v28, v25, s[0:1]
	v_rsq_f32_e32 v25, v25
	s_nop 0
	v_mul_f32_e32 v27, 0x45800000, v25
	v_cndmask_b32_e64 v25, v25, v27, s[0:1]
	v_mul_f32_e32 v25, v25, v26
	v_mul_f32_e32 v25, v12, v25
	v_mov_b32_e32 v26, v25
	v_mov_b32_e32 v255, v25
	s_nop 1
	v_permlane16_swap_b32_e32 v26, v255
	s_nop 1
	v_mov_b32_dpp v26, v255 quad_perm:[0,1,2,3] row_mask:0x5 bank_mask:0xf
	v_mul_f32_e32 v25, v23, v25
	v_cndmask_b32_e64 v26, v26, -v26, vcc
	v_fmac_f32_e32 v25, v24, v26
	v_mul_f32_e32 v25, 0x3e000000, v25
	v_cvt_pk_bf16_f32 v25, v25, s0
	global_store_short v[10:11], v25, off offset:640
	s_waitcnt vmcnt(9)
	v_mov_b32_e32 v25, v82
	v_lshlrev_b32_e32 v27, 16, v25
	s_waitcnt vmcnt(8)
	v_mov_b32_e32 v26, v83
	v_lshlrev_b32_e32 v26, 16, v26
	v_pk_mul_f32 v[28:29], v[26:27], v[26:27]
	v_mov_b32_e32 v255, v29
	s_nop 1
	v_permlane32_swap_b32_e32 v29, v255
	s_nop 1
	v_mov_b32_dpp v29, v255 quad_perm:[0,1,2,3] row_mask:0x3 bank_mask:0xf
	v_mov_b32_e32 v255, v28
	s_nop 1
	v_permlane32_swap_b32_e32 v28, v255
	s_nop 1
	v_mov_b32_dpp v28, v255 quad_perm:[0,1,2,3] row_mask:0x3 bank_mask:0xf
	v_pk_fma_f32 v[28:29], v[26:27], v[26:27], v[28:29]
	v_mov_b32_e32 v31, v29
	v_mov_b32_e32 v255, v29
	s_nop 1
	v_permlane16_swap_b32_e32 v31, v255
	s_nop 1
	v_mov_b32_dpp v31, v255 quad_perm:[0,1,2,3] row_mask:0x5 bank_mask:0xf
	v_mov_b32_e32 v30, v28
	v_mov_b32_e32 v255, v28
	s_nop 1
	v_permlane16_swap_b32_e32 v30, v255
	s_nop 1
	v_mov_b32_dpp v30, v255 quad_perm:[0,1,2,3] row_mask:0x5 bank_mask:0xf
	v_pk_add_f32 v[28:29], v[28:29], v[30:31]
	s_nop 1
	v_mov_b32_dpp v31, v29 row_ror:8 row_mask:0xf bank_mask:0xf
	v_mov_b32_dpp v30, v28 row_ror:8 row_mask:0xf bank_mask:0xf
	v_pk_add_f32 v[28:29], v[28:29], v[30:31]
	s_nop 1
	v_mov_b32_dpp v31, v29 row_shl:4 row_mask:0xf bank_mask:0x5
	v_mov_b32_dpp v31, v29 row_shr:4 row_mask:0xf bank_mask:0xa
	v_mov_b32_dpp v30, v28 row_shl:4 row_mask:0xf bank_mask:0x5
	v_mov_b32_dpp v30, v28 row_shr:4 row_mask:0xf bank_mask:0xa
	v_pk_add_f32 v[28:29], v[28:29], v[30:31]
	s_nop 1
	v_mov_b32_dpp v31, v29 quad_perm:[2,3,0,1] row_mask:0xf bank_mask:0xf
	v_mov_b32_dpp v30, v28 quad_perm:[2,3,0,1] row_mask:0xf bank_mask:0xf
	v_pk_add_f32 v[28:29], v[28:29], v[30:31]
	s_nop 1
	v_mov_b32_dpp v31, v29 quad_perm:[1,0,3,2] row_mask:0xf bank_mask:0xf
	v_mov_b32_dpp v30, v28 quad_perm:[1,0,3,2] row_mask:0xf bank_mask:0xf
	v_pk_add_f32 v[28:29], v[28:29], v[30:31]
	v_pk_fma_f32 v[28:29], v[28:29], s[10:11], v[8:9] op_sel_hi:[1,0,0]
	v_mul_f32_e32 v25, 0x4b800000, v29
	v_cmp_gt_f32_e64 s[40:41], s86, v29
	v_cmp_gt_f32_e64 s[0:1], s86, v28
	s_nop 0
	v_cndmask_b32_e64 v25, v29, v25, s[40:41]
	v_rsq_f32_e32 v25, v25
	s_nop 0
	v_mul_f32_e32 v29, 0x45800000, v25
	v_cndmask_b32_e64 v25, v25, v29, s[40:41]
	v_mul_f32_e32 v25, v25, v27
	v_mul_f32_e32 v25, v12, v25
	v_mov_b32_e32 v27, v25
	v_mov_b32_e32 v255, v25
	s_nop 1
	v_permlane16_swap_b32_e32 v27, v255
	s_nop 1
	v_mov_b32_dpp v27, v255 quad_perm:[0,1,2,3] row_mask:0x5 bank_mask:0xf
	v_mul_f32_e32 v25, v23, v25
	v_cndmask_b32_e64 v27, v27, -v27, vcc
	v_fmac_f32_e32 v25, v24, v27
	v_mul_f32_e32 v25, 0x3e000000, v25
	v_cvt_pk_bf16_f32 v25, v25, s0
	global_store_short v[10:11], v25, off offset:768
	v_mul_f32_e32 v25, 0x4b800000, v28
	v_cndmask_b32_e64 v25, v28, v25, s[0:1]
	v_rsq_f32_e32 v25, v25
	s_nop 0
	v_mul_f32_e32 v27, 0x45800000, v25
	v_cndmask_b32_e64 v25, v25, v27, s[0:1]
	v_mul_f32_e32 v25, v25, v26
	v_mul_f32_e32 v25, v12, v25
	v_mov_b32_e32 v26, v25
	v_mov_b32_e32 v255, v25
	s_nop 1
	v_permlane16_swap_b32_e32 v26, v255
	s_nop 1
	v_mov_b32_dpp v26, v255 quad_perm:[0,1,2,3] row_mask:0x5 bank_mask:0xf
	v_mul_f32_e32 v25, v23, v25
	v_cndmask_b32_e64 v26, v26, -v26, vcc
	v_fmac_f32_e32 v25, v24, v26
	v_mul_f32_e32 v25, 0x3e000000, v25
	v_cvt_pk_bf16_f32 v25, v25, s0
	global_store_short v[10:11], v25, off offset:896
	s_waitcnt vmcnt(9)
	v_mov_b32_e32 v10, v84
	v_lshlrev_b32_e32 v7, 16, v10
	s_waitcnt vmcnt(8)
	v_mov_b32_e32 v6, v85
	v_lshlrev_b32_e32 v6, 16, v6
	v_pk_mul_f32 v[10:11], v[6:7], v[6:7]
	v_mov_b32_e32 v255, v11
	s_nop 1
	v_permlane32_swap_b32_e32 v11, v255
	s_nop 1
	v_mov_b32_dpp v11, v255 quad_perm:[0,1,2,3] row_mask:0x3 bank_mask:0xf
	v_mov_b32_e32 v255, v10
	s_nop 1
	v_permlane32_swap_b32_e32 v10, v255
	s_nop 1
	v_mov_b32_dpp v10, v255 quad_perm:[0,1,2,3] row_mask:0x3 bank_mask:0xf
	v_pk_fma_f32 v[10:11], v[6:7], v[6:7], v[10:11]
	v_mov_b32_e32 v27, v11
	v_mov_b32_e32 v255, v11
	s_nop 1
	v_permlane16_swap_b32_e32 v27, v255
	s_nop 1
	v_mov_b32_dpp v27, v255 quad_perm:[0,1,2,3] row_mask:0x5 bank_mask:0xf
	v_mov_b32_e32 v26, v10
	v_mov_b32_e32 v255, v10
	s_nop 1
	v_permlane16_swap_b32_e32 v26, v255
	s_nop 1
	v_mov_b32_dpp v26, v255 quad_perm:[0,1,2,3] row_mask:0x5 bank_mask:0xf
	v_pk_add_f32 v[10:11], v[10:11], v[26:27]
	s_nop 1
	v_mov_b32_dpp v27, v11 row_ror:8 row_mask:0xf bank_mask:0xf
	v_mov_b32_dpp v26, v10 row_ror:8 row_mask:0xf bank_mask:0xf
	v_pk_add_f32 v[10:11], v[10:11], v[26:27]
	s_nop 1
	v_mov_b32_dpp v27, v11 row_shl:4 row_mask:0xf bank_mask:0x5
	v_mov_b32_dpp v27, v11 row_shr:4 row_mask:0xf bank_mask:0xa
	v_mov_b32_dpp v26, v10 row_shl:4 row_mask:0xf bank_mask:0x5
	v_mov_b32_dpp v26, v10 row_shr:4 row_mask:0xf bank_mask:0xa
	v_pk_add_f32 v[10:11], v[10:11], v[26:27]
	s_nop 1
	v_mov_b32_dpp v27, v11 quad_perm:[2,3,0,1] row_mask:0xf bank_mask:0xf
	v_mov_b32_dpp v26, v10 quad_perm:[2,3,0,1] row_mask:0xf bank_mask:0xf
	v_pk_add_f32 v[10:11], v[10:11], v[26:27]
	s_nop 1
	v_mov_b32_dpp v27, v11 quad_perm:[1,0,3,2] row_mask:0xf bank_mask:0xf
	v_mov_b32_dpp v26, v10 quad_perm:[1,0,3,2] row_mask:0xf bank_mask:0xf
	v_pk_add_f32 v[10:11], v[10:11], v[26:27]
	v_pk_fma_f32 v[8:9], v[10:11], s[10:11], v[8:9] op_sel_hi:[1,0,0]
	v_mul_f32_e32 v10, 0x4b800000, v9
	v_cmp_gt_f32_e64 s[40:41], s86, v9
	v_cmp_gt_f32_e64 s[0:1], s86, v8
	s_nop 0
	v_cndmask_b32_e64 v9, v9, v10, s[40:41]
	v_rsq_f32_e32 v9, v9
	s_nop 0
	v_mul_f32_e32 v10, 0x45800000, v9
	v_cndmask_b32_e64 v9, v9, v10, s[40:41]
	v_mul_f32_e32 v7, v9, v7
	v_mul_f32_e32 v7, v13, v7
	v_mov_b32_e32 v9, v7
	v_mov_b32_e32 v255, v7
	s_nop 1
	v_permlane16_swap_b32_e32 v9, v255
	s_nop 1
	v_mov_b32_dpp v9, v255 quad_perm:[0,1,2,3] row_mask:0x5 bank_mask:0xf
	v_mul_f32_e32 v7, v23, v7
	v_add_co_u32_e64 v4, s[40:41], s4, v4
	v_cndmask_b32_e64 v9, v9, -v9, vcc
	v_fmac_f32_e32 v7, v24, v9
	v_cvt_pk_bf16_f32 v7, v7, s0
	v_addc_co_u32_e64 v5, s[40:41], 0, v5, s[40:41]
	global_store_short v[4:5], v7, off
	v_mul_f32_e32 v7, 0x4b800000, v8
	v_cndmask_b32_e64 v7, v8, v7, s[0:1]
	v_rsq_f32_e32 v7, v7
	s_nop 0
	v_mul_f32_e32 v8, 0x45800000, v7
	v_cndmask_b32_e64 v7, v7, v8, s[0:1]
	v_mul_f32_e32 v6, v7, v6
	v_mul_f32_e32 v6, v13, v6
	v_mov_b32_e32 v7, v6
	v_mov_b32_e32 v255, v6
	s_nop 1
	v_permlane16_swap_b32_e32 v7, v255
	s_nop 1
	v_mov_b32_dpp v7, v255 quad_perm:[0,1,2,3] row_mask:0x5 bank_mask:0xf
	v_mul_f32_e32 v6, v23, v6
	v_cndmask_b32_e64 v7, v7, -v7, vcc
	v_fmac_f32_e32 v6, v24, v7
	v_cvt_pk_bf16_f32 v6, v6, s0
	global_store_short v[4:5], v6, off offset:128
	s_cbranch_scc0 .LBB0_543

.LBB0_580:
	v_add_u32_e32 v68, v67, v65
	ds_read_b128 v[72:75], v67 offset:18432
	ds_read_b128 v[76:79], v68
	s_add_i32 s0, s0, 32
	s_cmp_lt_u32 s0, 48
	s_waitcnt lgkmcnt(0)
	v_mfma_f32_32x32x16_bf16 v[48:63], v[76:79], v[72:75], v[48:63]
	ds_read_b128 v[72:75], v67 offset:23040
	s_waitcnt lgkmcnt(0)
	v_mfma_f32_32x32x16_bf16 v[16:31], v[76:79], v[72:75], v[16:31]
	ds_read_b128 v[72:75], v67 offset:27648
	s_waitcnt lgkmcnt(0)
	v_mfma_f32_32x32x16_bf16 v[32:47], v[76:79], v[72:75], v[32:47]
	ds_read_b128 v[72:75], v67 offset:32256
	ds_read_b128 v[80:83], v67 offset:18464
	s_waitcnt lgkmcnt(1)
	v_mfma_f32_32x32x16_bf16 v[0:15], v[76:79], v[72:75], v[0:15]
	ds_read_b128 v[72:75], v68 offset:32
	ds_read_b128 v[76:79], v67 offset:23072
	s_waitcnt lgkmcnt(0)
	v_mfma_f32_32x32x16_bf16 v[16:31], v[72:75], v[76:79], v[16:31]
	ds_read_b128 v[76:79], v67 offset:27680
	s_waitcnt lgkmcnt(0)
	v_mfma_f32_32x32x16_bf16 v[32:47], v[72:75], v[76:79], v[32:47]
	ds_read_b128 v[76:79], v67 offset:32288
	v_add_u32_e32 v67, 64, v67
	v_mfma_f32_32x32x16_bf16 v[48:63], v[72:75], v[80:83], v[48:63]
	s_waitcnt lgkmcnt(0)
	v_mfma_f32_32x32x16_bf16 v[0:15], v[72:75], v[76:79], v[0:15]
	s_cbranch_scc1 .LBB0_580
	s_lshl_b32 s0, s39, 9
	s_or_b32 s6, s0, s3
	v_or_b32_e32 v96, s6, v71
	v_readlane_b32 s8, v251, 20
	v_lshlrev_b32_e32 v67, 11, v64
	v_lshlrev_b64 v[64:65], 2, v[96:97]
	v_readlane_b32 s10, v251, 22
	v_readlane_b32 s11, v251, 23
	s_barrier
	s_nop 0
	v_lshl_add_u64 v[68:69], s[10:11], 0, v[64:65]
	v_readlane_b32 s100, v251, 16
	v_readlane_b32 s101, v251, 17
	s_nop 1
	v_lshl_add_u64 v[220:221], s[100:101], 0, v[64:65]
	v_readlane_b32 s100, v251, 20
	v_readlane_b32 s101, v251, 21
	s_nop 1
	v_lshl_add_u64 v[222:223], s[100:101], 0, v[64:65]
	global_load_dword v224, v[220:221], off
	global_load_dword v225, v[222:223], off
	global_load_dword v226, v[68:69], off offset:128
	global_load_dword v227, v[222:223], off offset:128
	global_load_dword v228, v[220:221], off offset:128
	global_load_dword v68, v[68:69], off
	s_mov_b32 s7, 0x3f2aaaab
	s_mov_b32 s39, 0x3f317218
	v_readlane_b32 s12, v251, 24
	v_readlane_b32 s13, v251, 25
	v_readlane_b32 s14, v251, 26
	v_readlane_b32 s15, v251, 27
	v_readlane_b32 s16, v251, 28
	v_readlane_b32 s17, v251, 29
	v_readlane_b32 s18, v251, 30
	v_readlane_b32 s19, v251, 31
	v_readlane_b32 s20, v251, 32
	v_readlane_b32 s21, v251, 33
	v_readlane_b32 s22, v251, 34
	v_readlane_b32 s23, v251, 35
	v_readlane_b32 s12, v251, 4
	v_readlane_b32 s24, v251, 16
	v_readlane_b32 s25, v251, 17
	v_readlane_b32 s9, v251, 21
	s_mov_b32 s40, 0x7f800000
	s_mov_b32 s41, 0x33800000
	v_readlane_b32 s15, v251, 7
	s_mov_b32 s15, 0x43000000
	v_readlane_b32 s16, v251, 8
	s_mov_b32 s16, 0x42b17217
	v_readlane_b32 s17, v251, 9
	s_mov_b32 s17, 0xf800000
	v_readlane_b32 s18, v251, 10
	s_mov_b32 s18, 0xc1880000
	v_add_u32_e32 v96, s6, v71
	s_cmp_eq_u32 s38, 0
	s_mov_b32 s4, 0
	v_readlane_b32 s13, v251, 5
	v_readlane_b32 s14, v251, 6
	v_readlane_b32 s19, v251, 11
	v_readlane_b32 s20, v251, 12
	v_readlane_b32 s21, v251, 13
	v_readlane_b32 s22, v251, 14
	v_readlane_b32 s23, v251, 15
	v_readlane_b32 s26, v251, 18
	v_readlane_b32 s27, v251, 19
	s_waitcnt vmcnt(0)
	v_mul_f32_e32 v68, 0xbfb8aa3b, v68
	v_exp_f32_e32 v70, v68
	s_nop 0
	v_add_f32_e32 v72, 1.0, v70
	v_add_f32_e32 v68, -1.0, v72
	v_sub_f32_e32 v69, v68, v72
	v_add_f32_e32 v69, 1.0, v69
	v_sub_f32_e32 v68, v70, v68
	v_add_f32_e32 v73, v68, v69
	v_frexp_mant_f32_e32 v68, v72
	v_cmp_gt_f32_e32 vcc, s7, v68
	v_cvt_f64_f32_e32 v[68:69], v72
	v_frexp_exp_i32_f64_e32 v68, v[68:69]
	v_subbrev_co_u32_e32 v78, vcc, 0, v68, vcc
	v_sub_u32_e32 v68, 0, v78
	v_ldexp_f32 v69, v72, v68
	v_add_f32_e32 v72, -1.0, v69
	v_add_f32_e32 v74, 1.0, v69
	v_ldexp_f32 v68, v73, v68
	v_add_f32_e32 v73, 1.0, v72
	v_add_f32_e32 v75, -1.0, v74
	v_sub_f32_e32 v73, v69, v73
	v_sub_f32_e32 v69, v69, v75
	v_add_f32_e32 v73, v68, v73
	v_add_f32_e32 v68, v68, v69
	v_add_f32_e32 v79, v74, v68
	v_rcp_f32_e32 v81, v79
	v_sub_f32_e32 v69, v79, v74
	v_sub_f32_e32 v80, v68, v69
	v_add_f32_e32 v69, v72, v73
	v_mul_f32_e32 v83, v69, v81
	v_sub_f32_e32 v68, v69, v72
	v_mul_f32_e32 v72, v79, v83
	v_fma_f32 v74, v83, v79, -v72
	v_fmac_f32_e32 v74, v83, v80
	v_sub_f32_e32 v82, v73, v68
	v_add_f32_e32 v68, v72, v74
	v_sub_f32_e32 v73, v69, v68
	v_pk_add_f32 v[76:77], v[68:69], v[72:73] neg_lo:[0,1] neg_hi:[0,1]
	v_mov_b32_e32 v75, v68
	v_pk_add_f32 v[68:69], v[76:77], v[74:75] neg_lo:[0,1] neg_hi:[0,1]
	v_cmp_neq_f32_e32 vcc, s40, v70
	v_add_f32_e32 v69, v82, v69
	v_add_f32_e32 v68, v68, v69
	v_add_f32_e32 v69, v73, v68
	v_mul_f32_e32 v82, v81, v69
	v_mul_f32_e32 v72, v79, v82
	v_fma_f32 v74, v82, v79, -v72
	v_fmac_f32_e32 v74, v82, v80
	v_sub_f32_e32 v73, v73, v69
	v_add_f32_e32 v79, v68, v73
	v_add_f32_e32 v68, v72, v74
	v_sub_f32_e32 v73, v69, v68
	v_pk_add_f32 v[76:77], v[68:69], v[72:73] neg_lo:[0,1] neg_hi:[0,1]
	v_mov_b32_e32 v75, v68
	v_pk_add_f32 v[68:69], v[76:77], v[74:75] neg_lo:[0,1] neg_hi:[0,1]
	v_add_f32_e32 v69, v79, v69
	v_add_f32_e32 v68, v68, v69
	v_add_f32_e32 v69, v83, v82
	v_add_f32_e32 v68, v73, v68
	v_sub_f32_e32 v72, v69, v83
	v_mul_f32_e32 v68, v81, v68
	v_sub_f32_e32 v72, v82, v72
	v_add_f32_e32 v72, v72, v68
	v_add_f32_e32 v74, v69, v72
	v_mul_f32_e32 v75, v74, v74
	v_fmamk_f32 v68, v75, 0x3e9b6dac, v191
	v_fmaak_f32 v169, v75, v68, 0x3f2aaada
	v_cvt_f32_i32_e32 v68, v78
	v_sub_f32_e32 v69, v74, v69
	v_sub_f32_e32 v69, v72, v69
	v_ldexp_f32 v76, v69, 1
	v_mul_f32_e32 v69, v74, v75
	v_ldexp_f32 v73, v74, 1
	v_pk_mul_f32 v[74:75], v[68:69], v[168:169]
	v_fma_f32 v72, v68, s39, -v74
	v_fmac_f32_e32 v72, 0xb102e308, v68
	v_pk_add_f32 v[68:69], v[74:75], v[72:73]
	v_sub_f32_e32 v73, v69, v73
	v_sub_f32_e32 v73, v75, v73
	v_add_f32_e32 v77, v76, v73
	v_mov_b32_e32 v76, v74
	v_pk_add_f32 v[74:75], v[68:69], v[74:75] neg_lo:[0,1] neg_hi:[0,1]
	v_pk_add_f32 v[78:79], v[68:69], v[76:77]
	v_mov_b32_e32 v73, v68
	v_mov_b32_e32 v75, v79
	v_pk_add_f32 v[80:81], v[72:73], v[74:75] neg_lo:[0,1] neg_hi:[0,1]
	v_pk_add_f32 v[72:73], v[72:73], v[74:75]
	v_mov_b32_e32 v76, v77
	v_pk_add_f32 v[74:75], v[72:73], v[68:69] op_sel:[1,0] op_sel_hi:[0,1] neg_lo:[0,1] neg_hi:[0,1]
	v_pk_add_f32 v[82:83], v[78:79], v[74:75] op_sel_hi:[1,0] neg_lo:[0,1] neg_hi:[0,1]
	v_mov_b32_e32 v78, v79
	v_mov_b32_e32 v79, v73
	v_pk_mov_b32 v[74:75], v[68:69], v[74:75] op_sel:[1,0]
	v_mov_b32_e32 v77, v68
	v_pk_add_f32 v[74:75], v[78:79], v[74:75] neg_lo:[0,1] neg_hi:[0,1]
	v_mov_b32_e32 v82, v80
	v_pk_add_f32 v[68:69], v[76:77], v[74:75] neg_lo:[0,1] neg_hi:[0,1]
	v_mov_b32_e32 v81, v73
	v_pk_add_f32 v[74:75], v[82:83], v[68:69]
	v_pk_add_f32 v[76:77], v[74:75], v[74:75] op_sel:[0,1] op_sel_hi:[1,0]
	v_pk_add_f32 v[72:73], v[72:73], v[76:77] op_sel:[1,0] op_sel_hi:[0,1]
	v_mov_b32_e32 v75, v72
	v_pk_add_f32 v[78:79], v[74:75], v[80:81] neg_lo:[0,1] neg_hi:[0,1]
	v_mov_b32_e32 v69, v76
	v_sub_f32_e32 v73, v74, v78
	v_pk_add_f32 v[68:69], v[68:69], v[78:79] neg_lo:[0,1] neg_hi:[0,1]
	v_sub_f32_e32 v73, v80, v73
	v_add_f32_e32 v68, v68, v73
	v_add_f32_e32 v68, v68, v69
	v_add_f32_e32 v68, v72, v68
	v_lshl_add_u64 v[72:73], s[24:25], 0, v[64:65]
	v_mov_b32_e32 v74, v224
	v_lshl_add_u64 v[64:65], s[8:9], 0, v[64:65]
	v_mov_b32_e32 v73, v225
	v_cndmask_b32_e32 v68, v199, v68, vcc
	v_cmp_ngt_f32_e32 vcc, -1.0, v70
	s_waitcnt vmcnt(1)
	v_add_f32_e32 v48, v48, v74
	v_mul_f32_e32 v48, 0xbfb8aa3b, v48
	v_exp_f32_e32 v48, v48
	v_cndmask_b32_e32 v68, v200, v68, vcc
	v_cmp_neq_f32_e32 vcc, -1.0, v70
	s_waitcnt vmcnt(0)
	v_add_f32_e32 v32, v32, v73
	v_add_f32_e32 v48, 1.0, v48
	v_rcp_f32_e32 v48, v48
	v_cndmask_b32_e32 v68, v201, v68, vcc
	v_cmp_lt_f32_e64 vcc, |v70|, s41
	v_mul_f32_e32 v32, 0xbfb8aa3b, v32
	v_exp_f32_e32 v32, v32
	v_cndmask_b32_e32 v68, v68, v70, vcc
	v_mul_f32_e32 v72, 0xc1000000, v68
	v_mul_f32_e32 v48, v48, v72
	v_mul_f32_e32 v64, 0x3fb8aa3b, v48
	v_add_f32_e32 v48, v48, v48
	v_exp_f32_e32 v68, v64
	v_mul_f32_e32 v64, 0x3fb8aa3b, v48
	v_rndne_f32_e32 v64, v64
	v_fmamk_f32 v65, v64, 0xbf317218, v48
	v_fmac_f32_e32 v65, 0x3102e308, v64
	v_fmamk_f32 v69, v65, 0x395133b1, v192
	v_cmp_eq_f32_e32 vcc, s15, v64
	v_cvt_i32_f32_e32 v64, v64
	v_fmaak_f32 v69, v65, v69, 0x3c0887f9
	v_fmaak_f32 v69, v65, v69, 0x3d2aaa81
	v_fmaak_f32 v69, v65, v69, 0x3e2aaaab
	v_fma_f32 v69, v65, v69, 0.5
	v_ldexp_f32 v64, 1.0, v64
	v_mul_f32_e32 v69, v65, v69
	v_cndmask_b32_e32 v64, v64, v202, vcc
	v_fmac_f32_e32 v65, v65, v69
	v_add_f32_e32 v69, -1.0, v64
	v_fmac_f32_e32 v69, v64, v65
	v_add_f32_e32 v64, v69, v69
	v_cndmask_b32_e32 v64, v69, v64, vcc
	v_cmp_nlt_f32_e32 vcc, s16, v48
	v_add_f32_e32 v32, 1.0, v32
	v_rcp_f32_e32 v32, v32
	v_cndmask_b32_e64 v64, v201, -v64, vcc
	v_cmp_gt_f32_e32 vcc, s17, v64
	v_mul_f32_e32 v65, 0x4f800000, v64
	v_add_f32_e32 v33, v33, v73
	v_cndmask_b32_e32 v64, v64, v65, vcc
	v_sqrt_f32_e32 v65, v64
	v_mul_f32_e32 v33, 0xbfb8aa3b, v33
	v_exp_f32_e32 v33, v33
	v_add_f32_e32 v34, v34, v73
	v_add_u32_e32 v69, -1, v65
	v_fma_f32 v70, -v69, v65, v64
	v_cmp_ge_f32_e64 s[0:1], 0, v70
	v_add_u32_e32 v70, 1, v65
	v_add_f32_e32 v33, 1.0, v33
	v_cndmask_b32_e64 v69, v65, v69, s[0:1]
	v_fma_f32 v65, -v70, v65, v64
	v_cmp_lt_f32_e64 s[0:1], 0, v65
	v_rcp_f32_e32 v33, v33
	v_mul_f32_e32 v34, 0xbfb8aa3b, v34
	v_cndmask_b32_e64 v65, v69, v70, s[0:1]
	v_mul_f32_e32 v69, 0x37800000, v65
	v_cndmask_b32_e32 v65, v65, v69, vcc
	v_cmp_class_f32_e32 vcc, v64, v193
	v_exp_f32_e32 v34, v34
	s_nop 0
	v_cndmask_b32_e32 v64, v65, v64, vcc
	v_cmp_ngt_f32_e32 vcc, s18, v48
	v_add_f32_e32 v34, 1.0, v34
	v_rcp_f32_e32 v34, v34
	v_cndmask_b32_e32 v48, 1.0, v64, vcc
	v_mul_f32_e32 v48, v32, v48
	v_and_b32_e32 v32, 0x100, v66
	v_or3_b32 v32, v67, v71, v32
	v_lshl_add_u32 v70, v32, 2, 0
	v_add_u32_e32 v32, 0x9000, v70
	ds_read2_b32 v[64:65], v32 offset1:32
	s_waitcnt lgkmcnt(0)
	v_mul_f32_e32 v48, v64, v48
	ds_write_b32 v70, v68
	ds_write_b32 v70, v48 offset:36864
	v_add_f32_e32 v48, v49, v74
	v_mul_f32_e32 v48, 0xbfb8aa3b, v48
	v_exp_f32_e32 v48, v48
	s_nop 0
	v_add_f32_e32 v48, 1.0, v48
	v_rcp_f32_e32 v48, v48
	s_nop 0
	v_mul_f32_e32 v48, v48, v72
	v_mul_f32_e32 v49, 0x3fb8aa3b, v48
	v_add_f32_e32 v48, v48, v48
	v_exp_f32_e32 v64, v49
	v_mul_f32_e32 v49, 0x3fb8aa3b, v48
	v_rndne_f32_e32 v49, v49
	v_fmamk_f32 v66, v49, 0xbf317218, v48
	v_fmac_f32_e32 v66, 0x3102e308, v49
	v_fmamk_f32 v67, v66, 0x395133b1, v192
	v_cmp_eq_f32_e32 vcc, s15, v49
	v_cvt_i32_f32_e32 v49, v49
	v_fmaak_f32 v67, v66, v67, 0x3c0887f9
	v_fmaak_f32 v67, v66, v67, 0x3d2aaa81
	v_fmaak_f32 v67, v66, v67, 0x3e2aaaab
	v_fma_f32 v67, v66, v67, 0.5
	v_ldexp_f32 v49, 1.0, v49
	v_mul_f32_e32 v67, v66, v67
	v_cndmask_b32_e32 v49, v49, v202, vcc
	v_fmac_f32_e32 v66, v66, v67
	v_add_f32_e32 v67, -1.0, v49
	v_fmac_f32_e32 v67, v49, v66
	v_add_f32_e32 v49, v67, v67
	v_cndmask_b32_e32 v49, v67, v49, vcc
	v_cmp_nlt_f32_e32 vcc, s16, v48
	s_nop 1
	v_cndmask_b32_e64 v49, v201, -v49, vcc
	v_cmp_gt_f32_e32 vcc, s17, v49
	v_mul_f32_e32 v66, 0x4f800000, v49
	s_nop 0
	v_cndmask_b32_e32 v49, v49, v66, vcc
	v_sqrt_f32_e32 v66, v49
	s_nop 0
	v_add_u32_e32 v67, -1, v66
	v_fma_f32 v68, -v67, v66, v49
	v_cmp_ge_f32_e64 s[0:1], 0, v68
	v_add_u32_e32 v68, 1, v66
	s_nop 0
	v_cndmask_b32_e64 v67, v66, v67, s[0:1]
	v_fma_f32 v66, -v68, v66, v49
	v_cmp_lt_f32_e64 s[0:1], 0, v66
	s_nop 1
	v_cndmask_b32_e64 v66, v67, v68, s[0:1]
	v_mul_f32_e32 v67, 0x37800000, v66
	v_cndmask_b32_e32 v66, v66, v67, vcc
	v_cmp_class_f32_e32 vcc, v49, v193
	s_nop 1
	v_cndmask_b32_e32 v49, v66, v49, vcc
	v_cmp_ngt_f32_e32 vcc, s18, v48
	s_nop 1
	v_cndmask_b32_e32 v48, 1.0, v49, vcc
	v_mul_f32_e32 v33, v33, v48
	ds_read2_b32 v[48:49], v32 offset0:64 offset1:96
	s_waitcnt lgkmcnt(0)
	v_mul_f32_e32 v33, v48, v33
	ds_write_b32 v70, v64 offset:256
	ds_write_b32 v70, v33 offset:37120
	v_add_f32_e32 v33, v50, v74
	v_mul_f32_e32 v33, 0xbfb8aa3b, v33
	v_exp_f32_e32 v33, v33
	s_nop 0
	v_add_f32_e32 v33, 1.0, v33
	v_rcp_f32_e32 v33, v33
	s_nop 0
	v_mul_f32_e32 v33, v33, v72
	v_mul_f32_e32 v48, 0x3fb8aa3b, v33
	v_add_f32_e32 v33, v33, v33
	v_mul_f32_e32 v50, 0x3fb8aa3b, v33
	v_rndne_f32_e32 v50, v50
	v_fmamk_f32 v64, v50, 0xbf317218, v33
	v_fmac_f32_e32 v64, 0x3102e308, v50
	v_fmamk_f32 v66, v64, 0x395133b1, v192
	v_cmp_eq_f32_e32 vcc, s15, v50
	v_cvt_i32_f32_e32 v50, v50
	v_fmaak_f32 v66, v64, v66, 0x3c0887f9
	v_fmaak_f32 v66, v64, v66, 0x3d2aaa81
	v_fmaak_f32 v66, v64, v66, 0x3e2aaaab
	v_fma_f32 v66, v64, v66, 0.5
	v_ldexp_f32 v50, 1.0, v50
	v_mul_f32_e32 v66, v64, v66
	v_cndmask_b32_e32 v50, v50, v202, vcc
	v_fmac_f32_e32 v64, v64, v66
	v_add_f32_e32 v66, -1.0, v50
	v_fmac_f32_e32 v66, v50, v64
	v_add_f32_e32 v50, v66, v66
	v_cndmask_b32_e32 v50, v66, v50, vcc
	v_cmp_nlt_f32_e32 vcc, s16, v33
	v_exp_f32_e32 v48, v48
	s_nop 0
	v_cndmask_b32_e64 v50, v201, -v50, vcc
	v_cmp_gt_f32_e32 vcc, s17, v50
	v_mul_f32_e32 v64, 0x4f800000, v50
	s_nop 0
	v_cndmask_b32_e32 v50, v50, v64, vcc
	v_sqrt_f32_e32 v64, v50
	s_nop 0
	v_add_u32_e32 v66, -1, v64
	v_fma_f32 v67, -v66, v64, v50
	v_cmp_ge_f32_e64 s[0:1], 0, v67
	v_add_u32_e32 v67, 1, v64
	s_nop 0
	v_cndmask_b32_e64 v66, v64, v66, s[0:1]
	v_fma_f32 v64, -v67, v64, v50
	v_cmp_lt_f32_e64 s[0:1], 0, v64
	s_nop 1
	v_cndmask_b32_e64 v64, v66, v67, s[0:1]
	v_mul_f32_e32 v66, 0x37800000, v64
	v_cndmask_b32_e32 v64, v64, v66, vcc
	ds_read2_b32 v[66:67], v32 offset0:128 offset1:160
	v_cmp_class_f32_e32 vcc, v50, v193
	s_nop 1
	v_cndmask_b32_e32 v50, v64, v50, vcc
	v_cmp_ngt_f32_e32 vcc, s18, v33
	s_nop 1
	v_cndmask_b32_e32 v33, 1.0, v50, vcc
	v_mul_f32_e32 v33, v34, v33
	s_waitcnt lgkmcnt(0)
	v_mul_f32_e32 v33, v66, v33
	ds_write_b32 v70, v48 offset:512
	ds_write_b32 v70, v33 offset:37376
	v_add_f32_e32 v33, v51, v74
	v_mul_f32_e32 v33, 0xbfb8aa3b, v33
	v_exp_f32_e32 v33, v33
	v_add_f32_e32 v34, v35, v73
	v_mul_f32_e32 v34, 0xbfb8aa3b, v34
	v_exp_f32_e32 v34, v34
	v_add_f32_e32 v33, 1.0, v33
	v_rcp_f32_e32 v33, v33
	v_add_f32_e32 v34, 1.0, v34
	v_rcp_f32_e32 v34, v34
	v_mul_f32_e32 v33, v33, v72
	v_mul_f32_e32 v35, 0x3fb8aa3b, v33
	v_add_f32_e32 v33, v33, v33
	v_mul_f32_e32 v48, 0x3fb8aa3b, v33
	v_rndne_f32_e32 v48, v48
	v_fmamk_f32 v50, v48, 0xbf317218, v33
	v_fmac_f32_e32 v50, 0x3102e308, v48
	v_fmamk_f32 v51, v50, 0x395133b1, v192
	v_cmp_eq_f32_e32 vcc, s15, v48
	v_cvt_i32_f32_e32 v48, v48
	v_fmaak_f32 v51, v50, v51, 0x3c0887f9
	v_fmaak_f32 v51, v50, v51, 0x3d2aaa81
	v_fmaak_f32 v51, v50, v51, 0x3e2aaaab
	v_fma_f32 v51, v50, v51, 0.5
	v_ldexp_f32 v48, 1.0, v48
	v_mul_f32_e32 v51, v50, v51
	v_cndmask_b32_e32 v48, v48, v202, vcc
	v_fmac_f32_e32 v50, v50, v51
	v_add_f32_e32 v51, -1.0, v48
	v_fmac_f32_e32 v51, v48, v50
	v_add_f32_e32 v48, v51, v51
	v_cndmask_b32_e32 v48, v51, v48, vcc
	v_cmp_nlt_f32_e32 vcc, s16, v33
	v_exp_f32_e32 v35, v35
	s_nop 0
	v_cndmask_b32_e64 v48, v201, -v48, vcc
	v_cmp_gt_f32_e32 vcc, s17, v48
	v_mul_f32_e32 v50, 0x4f800000, v48
	s_nop 0
	v_cndmask_b32_e32 v48, v48, v50, vcc
	v_sqrt_f32_e32 v50, v48
	s_nop 0
	v_add_u32_e32 v51, -1, v50
	v_fma_f32 v64, -v51, v50, v48
	v_cmp_ge_f32_e64 s[0:1], 0, v64
	v_add_u32_e32 v64, 1, v50
	s_nop 0
	v_cndmask_b32_e64 v51, v50, v51, s[0:1]
	v_fma_f32 v50, -v64, v50, v48
	v_cmp_lt_f32_e64 s[0:1], 0, v50
	s_nop 1
	v_cndmask_b32_e64 v50, v51, v64, s[0:1]
	v_mul_f32_e32 v51, 0x37800000, v50
	v_cndmask_b32_e32 v50, v50, v51, vcc
	v_cmp_class_f32_e32 vcc, v48, v193
	s_nop 1
	v_cndmask_b32_e32 v48, v50, v48, vcc
	ds_read2_b32 v[50:51], v32 offset0:192 offset1:224
	v_cmp_ngt_f32_e32 vcc, s18, v33
	s_nop 1
	v_cndmask_b32_e32 v33, 1.0, v48, vcc
	v_mul_f32_e32 v33, v34, v33
	s_waitcnt lgkmcnt(0)
	v_mul_f32_e32 v32, v50, v33
	ds_write_b32 v70, v35 offset:768
	ds_write_b32 v70, v32 offset:37632
	v_add_f32_e32 v32, v52, v74
	v_mul_f32_e32 v32, 0xbfb8aa3b, v32
	v_exp_f32_e32 v32, v32
	v_add_f32_e32 v33, v36, v73
	v_mul_f32_e32 v33, 0xbfb8aa3b, v33
	v_exp_f32_e32 v33, v33
	v_add_f32_e32 v32, 1.0, v32
	v_rcp_f32_e32 v32, v32
	v_add_f32_e32 v33, 1.0, v33
	v_rcp_f32_e32 v33, v33
	v_mul_f32_e32 v32, v32, v72
	v_mul_f32_e32 v34, 0x3fb8aa3b, v32
	v_add_f32_e32 v32, v32, v32
	v_mul_f32_e32 v35, 0x3fb8aa3b, v32
	v_rndne_f32_e32 v35, v35
	v_fmamk_f32 v36, v35, 0xbf317218, v32
	v_fmac_f32_e32 v36, 0x3102e308, v35
	v_fmamk_f32 v48, v36, 0x395133b1, v192
	v_cmp_eq_f32_e32 vcc, s15, v35
	v_cvt_i32_f32_e32 v35, v35
	v_fmaak_f32 v48, v36, v48, 0x3c0887f9
	v_fmaak_f32 v48, v36, v48, 0x3d2aaa81
	v_fmaak_f32 v48, v36, v48, 0x3e2aaaab
	v_fma_f32 v48, v36, v48, 0.5
	v_ldexp_f32 v35, 1.0, v35
	v_mul_f32_e32 v48, v36, v48
	v_cndmask_b32_e32 v35, v35, v202, vcc
	v_fmac_f32_e32 v36, v36, v48
	v_add_f32_e32 v48, -1.0, v35
	v_fmac_f32_e32 v48, v35, v36
	v_add_f32_e32 v35, v48, v48
	v_cndmask_b32_e32 v35, v48, v35, vcc
	v_cmp_nlt_f32_e32 vcc, s16, v32
	v_exp_f32_e32 v34, v34
	s_nop 0
	v_cndmask_b32_e64 v35, v201, -v35, vcc
	v_cmp_gt_f32_e32 vcc, s17, v35
	v_mul_f32_e32 v36, 0x4f800000, v35
	s_nop 0
	v_cndmask_b32_e32 v35, v35, v36, vcc
	v_sqrt_f32_e32 v36, v35
	s_nop 0
	v_add_u32_e32 v48, -1, v36
	v_fma_f32 v50, -v48, v36, v35
	v_cmp_ge_f32_e64 s[0:1], 0, v50
	v_add_u32_e32 v50, 1, v36
	s_nop 0
	v_cndmask_b32_e64 v48, v36, v48, s[0:1]
	v_fma_f32 v36, -v50, v36, v35
	v_cmp_lt_f32_e64 s[0:1], 0, v36
	s_nop 1
	v_cndmask_b32_e64 v36, v48, v50, s[0:1]
	v_mul_f32_e32 v48, 0x37800000, v36
	v_cndmask_b32_e32 v36, v36, v48, vcc
	v_cmp_class_f32_e32 vcc, v35, v193
	s_nop 1
	v_cndmask_b32_e32 v35, v36, v35, vcc
	v_cmp_ngt_f32_e32 vcc, s18, v32
	s_nop 1
	v_cndmask_b32_e32 v32, 1.0, v35, vcc
	v_mul_f32_e32 v33, v33, v32
	v_add_u32_e32 v32, 0x9800, v70
	ds_read2_b32 v[68:69], v32 offset1:32
	s_waitcnt lgkmcnt(0)
	v_mul_f32_e32 v33, v68, v33
	ds_write_b32 v70, v34 offset:2048
	ds_write_b32 v70, v33 offset:38912
	v_add_f32_e32 v33, v53, v74
	v_mul_f32_e32 v33, 0xbfb8aa3b, v33
	v_exp_f32_e32 v33, v33
	v_add_f32_e32 v34, v37, v73
	v_mul_f32_e32 v34, 0xbfb8aa3b, v34
	v_exp_f32_e32 v34, v34
	v_add_f32_e32 v33, 1.0, v33
	v_rcp_f32_e32 v33, v33
	v_add_f32_e32 v34, 1.0, v34
	v_rcp_f32_e32 v34, v34
	v_mul_f32_e32 v33, v33, v72
	v_mul_f32_e32 v35, 0x3fb8aa3b, v33
	v_add_f32_e32 v33, v33, v33
	v_mul_f32_e32 v36, 0x3fb8aa3b, v33
	v_rndne_f32_e32 v36, v36
	v_fmamk_f32 v37, v36, 0xbf317218, v33
	v_fmac_f32_e32 v37, 0x3102e308, v36
	v_fmamk_f32 v48, v37, 0x395133b1, v192
	v_cmp_eq_f32_e32 vcc, s15, v36
	v_cvt_i32_f32_e32 v36, v36
	v_fmaak_f32 v48, v37, v48, 0x3c0887f9
	v_fmaak_f32 v48, v37, v48, 0x3d2aaa81
	v_fmaak_f32 v48, v37, v48, 0x3e2aaaab
	v_fma_f32 v48, v37, v48, 0.5
	v_ldexp_f32 v36, 1.0, v36
	v_mul_f32_e32 v48, v37, v48
	v_cndmask_b32_e32 v36, v36, v202, vcc
	v_fmac_f32_e32 v37, v37, v48
	v_add_f32_e32 v48, -1.0, v36
	v_fmac_f32_e32 v48, v36, v37
	v_add_f32_e32 v36, v48, v48
	v_cndmask_b32_e32 v36, v48, v36, vcc
	v_cmp_nlt_f32_e32 vcc, s16, v33
	v_exp_f32_e32 v35, v35
	s_nop 0
	v_cndmask_b32_e64 v36, v201, -v36, vcc
	v_cmp_gt_f32_e32 vcc, s17, v36
	v_mul_f32_e32 v37, 0x4f800000, v36
	s_nop 0
	v_cndmask_b32_e32 v36, v36, v37, vcc
	v_sqrt_f32_e32 v37, v36
	s_nop 0
	v_add_u32_e32 v48, -1, v37
	v_fma_f32 v50, -v48, v37, v36
	v_cmp_ge_f32_e64 s[0:1], 0, v50
	v_add_u32_e32 v50, 1, v37
	s_nop 0
	v_cndmask_b32_e64 v48, v37, v48, s[0:1]
	v_fma_f32 v37, -v50, v37, v36
	v_cmp_lt_f32_e64 s[0:1], 0, v37
	s_nop 1
	v_cndmask_b32_e64 v37, v48, v50, s[0:1]
	v_mul_f32_e32 v48, 0x37800000, v37
	v_cndmask_b32_e32 v37, v37, v48, vcc
	v_cmp_class_f32_e32 vcc, v36, v193
	s_nop 1
	v_cndmask_b32_e32 v36, v37, v36, vcc
	v_cmp_ngt_f32_e32 vcc, s18, v33
	s_nop 1
	v_cndmask_b32_e32 v33, 1.0, v36, vcc
	ds_read2_b32 v[36:37], v32 offset0:64 offset1:96
	v_mul_f32_e32 v33, v34, v33
	v_add_f32_e32 v34, v38, v73
	v_mul_f32_e32 v34, 0xbfb8aa3b, v34
	v_exp_f32_e32 v34, v34
	s_waitcnt lgkmcnt(0)
	v_mul_f32_e32 v33, v36, v33
	ds_write_b32 v70, v35 offset:2304
	ds_write_b32 v70, v33 offset:39168
	v_add_f32_e32 v33, v54, v74
	v_mul_f32_e32 v33, 0xbfb8aa3b, v33
	v_exp_f32_e32 v33, v33
	v_add_f32_e32 v34, 1.0, v34
	v_rcp_f32_e32 v34, v34
	ds_read2_b32 v[52:53], v32 offset0:128 offset1:160
	v_add_f32_e32 v33, 1.0, v33
	v_rcp_f32_e32 v33, v33
	s_nop 0
	v_mul_f32_e32 v33, v33, v72
	v_mul_f32_e32 v35, 0x3fb8aa3b, v33
	v_add_f32_e32 v33, v33, v33
	v_mul_f32_e32 v36, 0x3fb8aa3b, v33
	v_rndne_f32_e32 v36, v36
	v_fmamk_f32 v38, v36, 0xbf317218, v33
	v_fmac_f32_e32 v38, 0x3102e308, v36
	v_fmamk_f32 v48, v38, 0x395133b1, v192
	v_cmp_eq_f32_e32 vcc, s15, v36
	v_cvt_i32_f32_e32 v36, v36
	v_fmaak_f32 v48, v38, v48, 0x3c0887f9
	v_fmaak_f32 v48, v38, v48, 0x3d2aaa81
	v_fmaak_f32 v48, v38, v48, 0x3e2aaaab
	v_fma_f32 v48, v38, v48, 0.5
	v_ldexp_f32 v36, 1.0, v36
	v_mul_f32_e32 v48, v38, v48
	v_cndmask_b32_e32 v36, v36, v202, vcc
	v_fmac_f32_e32 v38, v38, v48
	v_add_f32_e32 v48, -1.0, v36
	v_fmac_f32_e32 v48, v36, v38
	v_add_f32_e32 v36, v48, v48
	v_cndmask_b32_e32 v36, v48, v36, vcc
	v_cmp_nlt_f32_e32 vcc, s16, v33
	v_exp_f32_e32 v35, v35
	s_nop 0
	v_cndmask_b32_e64 v36, v201, -v36, vcc
	v_cmp_gt_f32_e32 vcc, s17, v36
	v_mul_f32_e32 v38, 0x4f800000, v36
	s_nop 0
	v_cndmask_b32_e32 v36, v36, v38, vcc
	v_sqrt_f32_e32 v38, v36
	s_nop 0
	v_add_u32_e32 v48, -1, v38
	v_fma_f32 v50, -v48, v38, v36
	v_cmp_ge_f32_e64 s[0:1], 0, v50
	v_add_u32_e32 v50, 1, v38
	s_nop 0
	v_cndmask_b32_e64 v48, v38, v48, s[0:1]
	v_fma_f32 v38, -v50, v38, v36
	v_cmp_lt_f32_e64 s[0:1], 0, v38
	s_nop 1
	v_cndmask_b32_e64 v38, v48, v50, s[0:1]
	v_mul_f32_e32 v48, 0x37800000, v38
	v_cndmask_b32_e32 v38, v38, v48, vcc
	v_cmp_class_f32_e32 vcc, v36, v193
	s_nop 1
	v_cndmask_b32_e32 v36, v38, v36, vcc
	v_cmp_ngt_f32_e32 vcc, s18, v33
	s_nop 1
	v_cndmask_b32_e32 v33, 1.0, v36, vcc
	v_mul_f32_e32 v33, v34, v33
	s_waitcnt lgkmcnt(0)
	v_mul_f32_e32 v33, v52, v33
	ds_write_b32 v70, v35 offset:2560
	ds_write_b32 v70, v33 offset:39424
	v_add_f32_e32 v33, v55, v74
	v_mul_f32_e32 v33, 0xbfb8aa3b, v33
	v_exp_f32_e32 v33, v33
	v_add_f32_e32 v34, v39, v73
	v_mul_f32_e32 v34, 0xbfb8aa3b, v34
	v_exp_f32_e32 v34, v34
	v_add_f32_e32 v33, 1.0, v33
	v_rcp_f32_e32 v33, v33
	v_add_f32_e32 v34, 1.0, v34
	v_rcp_f32_e32 v34, v34
	v_mul_f32_e32 v33, v33, v72
	v_mul_f32_e32 v35, 0x3fb8aa3b, v33
	v_add_f32_e32 v33, v33, v33
	v_mul_f32_e32 v36, 0x3fb8aa3b, v33
	v_rndne_f32_e32 v36, v36
	v_fmamk_f32 v38, v36, 0xbf317218, v33
	v_fmac_f32_e32 v38, 0x3102e308, v36
	v_fmamk_f32 v39, v38, 0x395133b1, v192
	v_cmp_eq_f32_e32 vcc, s15, v36
	v_cvt_i32_f32_e32 v36, v36
	v_fmaak_f32 v39, v38, v39, 0x3c0887f9
	v_fmaak_f32 v39, v38, v39, 0x3d2aaa81
	v_fmaak_f32 v39, v38, v39, 0x3e2aaaab
	v_fma_f32 v39, v38, v39, 0.5
	v_ldexp_f32 v36, 1.0, v36
	v_mul_f32_e32 v39, v38, v39
	v_cndmask_b32_e32 v36, v36, v202, vcc
	v_fmac_f32_e32 v38, v38, v39
	v_add_f32_e32 v39, -1.0, v36
	v_fmac_f32_e32 v39, v36, v38
	v_add_f32_e32 v36, v39, v39
	v_cndmask_b32_e32 v36, v39, v36, vcc
	v_cmp_nlt_f32_e32 vcc, s16, v33
	v_exp_f32_e32 v35, v35
	s_nop 0
	v_cndmask_b32_e64 v36, v201, -v36, vcc
	v_cmp_gt_f32_e32 vcc, s17, v36
	v_mul_f32_e32 v38, 0x4f800000, v36
	s_nop 0
	v_cndmask_b32_e32 v36, v36, v38, vcc
	v_sqrt_f32_e32 v38, v36
	s_nop 0
	v_add_u32_e32 v39, -1, v38
	v_fma_f32 v48, -v39, v38, v36
	v_cmp_ge_f32_e64 s[0:1], 0, v48
	v_add_u32_e32 v48, 1, v38
	s_nop 0
	v_cndmask_b32_e64 v39, v38, v39, s[0:1]
	v_fma_f32 v38, -v48, v38, v36
	v_cmp_lt_f32_e64 s[0:1], 0, v38
	s_nop 1
	v_cndmask_b32_e64 v38, v39, v48, s[0:1]
	v_mul_f32_e32 v39, 0x37800000, v38
	v_cndmask_b32_e32 v38, v38, v39, vcc
	v_cmp_class_f32_e32 vcc, v36, v193
	s_nop 1
	v_cndmask_b32_e32 v36, v38, v36, vcc
	ds_read2_b32 v[38:39], v32 offset0:192 offset1:224
	v_cmp_ngt_f32_e32 vcc, s18, v33
	s_nop 1
	v_cndmask_b32_e32 v33, 1.0, v36, vcc
	v_mul_f32_e32 v33, v34, v33
	s_waitcnt lgkmcnt(0)
	v_mul_f32_e32 v32, v38, v33
	ds_write_b32 v70, v35 offset:2816
	ds_write_b32 v70, v32 offset:39680
	v_add_f32_e32 v32, v56, v74
	v_mul_f32_e32 v32, 0xbfb8aa3b, v32
	v_exp_f32_e32 v32, v32
	v_add_f32_e32 v33, v40, v73
	v_mul_f32_e32 v33, 0xbfb8aa3b, v33
	v_exp_f32_e32 v33, v33
	v_add_f32_e32 v32, 1.0, v32
	v_rcp_f32_e32 v32, v32
	v_add_f32_e32 v33, 1.0, v33
	v_rcp_f32_e32 v33, v33
	v_mul_f32_e32 v32, v32, v72
	v_mul_f32_e32 v34, 0x3fb8aa3b, v32
	v_add_f32_e32 v32, v32, v32
	v_mul_f32_e32 v35, 0x3fb8aa3b, v32
	v_rndne_f32_e32 v35, v35
	v_fmamk_f32 v36, v35, 0xbf317218, v32
	v_fmac_f32_e32 v36, 0x3102e308, v35
	v_fmamk_f32 v38, v36, 0x395133b1, v192
	v_cmp_eq_f32_e32 vcc, s15, v35
	v_cvt_i32_f32_e32 v35, v35
	v_fmaak_f32 v38, v36, v38, 0x3c0887f9
	v_fmaak_f32 v38, v36, v38, 0x3d2aaa81
	v_fmaak_f32 v38, v36, v38, 0x3e2aaaab
	v_fma_f32 v38, v36, v38, 0.5
	v_ldexp_f32 v35, 1.0, v35
	v_mul_f32_e32 v38, v36, v38
	v_cndmask_b32_e32 v35, v35, v202, vcc
	v_fmac_f32_e32 v36, v36, v38
	v_add_f32_e32 v38, -1.0, v35
	v_fmac_f32_e32 v38, v35, v36
	v_add_f32_e32 v35, v38, v38
	v_cndmask_b32_e32 v35, v38, v35, vcc
	v_cmp_nlt_f32_e32 vcc, s16, v32
	v_exp_f32_e32 v34, v34
	s_nop 0
	v_cndmask_b32_e64 v35, v201, -v35, vcc
	v_cmp_gt_f32_e32 vcc, s17, v35
	v_mul_f32_e32 v36, 0x4f800000, v35
	s_nop 0
	v_cndmask_b32_e32 v35, v35, v36, vcc
	v_sqrt_f32_e32 v36, v35
	s_nop 0
	v_add_u32_e32 v38, -1, v36
	v_fma_f32 v40, -v38, v36, v35
	v_cmp_ge_f32_e64 s[0:1], 0, v40
	v_add_u32_e32 v40, 1, v36
	s_nop 0
	v_cndmask_b32_e64 v38, v36, v38, s[0:1]
	v_fma_f32 v36, -v40, v36, v35
	v_cmp_lt_f32_e64 s[0:1], 0, v36
	s_nop 1
	v_cndmask_b32_e64 v36, v38, v40, s[0:1]
	v_mul_f32_e32 v38, 0x37800000, v36
	v_cndmask_b32_e32 v36, v36, v38, vcc
	v_cmp_class_f32_e32 vcc, v35, v193
	s_nop 1
	v_cndmask_b32_e32 v35, v36, v35, vcc
	v_cmp_ngt_f32_e32 vcc, s18, v32
	s_nop 1
	v_cndmask_b32_e32 v32, 1.0, v35, vcc
	v_mul_f32_e32 v33, v33, v32
	v_add_u32_e32 v32, 0xa000, v70
	ds_read2_b32 v[54:55], v32 offset1:32
	s_waitcnt lgkmcnt(0)
	v_mul_f32_e32 v33, v54, v33
	ds_write_b32 v70, v34 offset:4096
	ds_write_b32 v70, v33 offset:40960
	v_add_f32_e32 v33, v57, v74
	v_mul_f32_e32 v33, 0xbfb8aa3b, v33
	v_exp_f32_e32 v33, v33
	v_add_f32_e32 v34, v41, v73
	v_mul_f32_e32 v34, 0xbfb8aa3b, v34
	v_exp_f32_e32 v34, v34
	v_add_f32_e32 v33, 1.0, v33
	v_rcp_f32_e32 v33, v33
	v_add_f32_e32 v34, 1.0, v34
	v_rcp_f32_e32 v34, v34
	v_mul_f32_e32 v33, v33, v72
	v_mul_f32_e32 v35, 0x3fb8aa3b, v33
	v_add_f32_e32 v33, v33, v33
	v_mul_f32_e32 v36, 0x3fb8aa3b, v33
	v_rndne_f32_e32 v36, v36
	v_fmamk_f32 v38, v36, 0xbf317218, v33
	v_fmac_f32_e32 v38, 0x3102e308, v36
	v_fmamk_f32 v40, v38, 0x395133b1, v192
	v_cmp_eq_f32_e32 vcc, s15, v36
	v_cvt_i32_f32_e32 v36, v36
	v_fmaak_f32 v40, v38, v40, 0x3c0887f9
	v_fmaak_f32 v40, v38, v40, 0x3d2aaa81
	v_fmaak_f32 v40, v38, v40, 0x3e2aaaab
	v_fma_f32 v40, v38, v40, 0.5
	v_ldexp_f32 v36, 1.0, v36
	v_mul_f32_e32 v40, v38, v40
	v_cndmask_b32_e32 v36, v36, v202, vcc
	v_fmac_f32_e32 v38, v38, v40
	v_add_f32_e32 v40, -1.0, v36
	v_fmac_f32_e32 v40, v36, v38
	v_add_f32_e32 v36, v40, v40
	v_cndmask_b32_e32 v36, v40, v36, vcc
	v_cmp_nlt_f32_e32 vcc, s16, v33
	v_exp_f32_e32 v35, v35
	s_nop 0
	v_cndmask_b32_e64 v36, v201, -v36, vcc
	v_cmp_gt_f32_e32 vcc, s17, v36
	v_mul_f32_e32 v38, 0x4f800000, v36
	s_nop 0
	v_cndmask_b32_e32 v36, v36, v38, vcc
	v_sqrt_f32_e32 v38, v36
	s_nop 0
	v_add_u32_e32 v40, -1, v38
	v_fma_f32 v41, -v40, v38, v36
	v_cmp_ge_f32_e64 s[0:1], 0, v41
	v_add_u32_e32 v41, 1, v38
	s_nop 0
	v_cndmask_b32_e64 v40, v38, v40, s[0:1]
	v_fma_f32 v38, -v41, v38, v36
	v_cmp_lt_f32_e64 s[0:1], 0, v38
	s_nop 1
	v_cndmask_b32_e64 v38, v40, v41, s[0:1]
	v_mul_f32_e32 v40, 0x37800000, v38
	v_cndmask_b32_e32 v38, v38, v40, vcc
	ds_read2_b32 v[40:41], v32 offset0:64 offset1:96
	v_cmp_class_f32_e32 vcc, v36, v193
	s_nop 1
	v_cndmask_b32_e32 v36, v38, v36, vcc
	v_cmp_ngt_f32_e32 vcc, s18, v33
	s_nop 1
	v_cndmask_b32_e32 v33, 1.0, v36, vcc
	v_mul_f32_e32 v33, v34, v33
	s_waitcnt lgkmcnt(0)
	v_mul_f32_e32 v33, v40, v33
	ds_write_b32 v70, v35 offset:4352
	ds_write_b32 v70, v33 offset:41216
	v_add_f32_e32 v33, v58, v74
	v_mul_f32_e32 v33, 0xbfb8aa3b, v33
	v_exp_f32_e32 v33, v33
	v_add_f32_e32 v34, v42, v73
	v_mul_f32_e32 v34, 0xbfb8aa3b, v34
	v_exp_f32_e32 v34, v34
	v_add_f32_e32 v33, 1.0, v33
	v_rcp_f32_e32 v33, v33
	ds_read2_b32 v[56:57], v32 offset0:128 offset1:160
	v_add_f32_e32 v34, 1.0, v34
	v_rcp_f32_e32 v34, v34
	v_mul_f32_e32 v33, v33, v72
	v_mul_f32_e32 v35, 0x3fb8aa3b, v33
	v_add_f32_e32 v33, v33, v33
	v_mul_f32_e32 v36, 0x3fb8aa3b, v33
	v_rndne_f32_e32 v36, v36
	v_fmamk_f32 v38, v36, 0xbf317218, v33
	v_fmac_f32_e32 v38, 0x3102e308, v36
	v_fmamk_f32 v40, v38, 0x395133b1, v192
	v_cmp_eq_f32_e32 vcc, s15, v36
	v_cvt_i32_f32_e32 v36, v36
	v_fmaak_f32 v40, v38, v40, 0x3c0887f9
	v_fmaak_f32 v40, v38, v40, 0x3d2aaa81
	v_fmaak_f32 v40, v38, v40, 0x3e2aaaab
	v_fma_f32 v40, v38, v40, 0.5
	v_ldexp_f32 v36, 1.0, v36
	v_mul_f32_e32 v40, v38, v40
	v_cndmask_b32_e32 v36, v36, v202, vcc
	v_fmac_f32_e32 v38, v38, v40
	v_add_f32_e32 v40, -1.0, v36
	v_fmac_f32_e32 v40, v36, v38
	v_add_f32_e32 v36, v40, v40
	v_cndmask_b32_e32 v36, v40, v36, vcc
	v_cmp_nlt_f32_e32 vcc, s16, v33
	v_exp_f32_e32 v35, v35
	s_nop 0
	v_cndmask_b32_e64 v36, v201, -v36, vcc
	v_cmp_gt_f32_e32 vcc, s17, v36
	v_mul_f32_e32 v38, 0x4f800000, v36
	s_nop 0
	v_cndmask_b32_e32 v36, v36, v38, vcc
	v_sqrt_f32_e32 v38, v36
	s_nop 0
	v_add_u32_e32 v40, -1, v38
	v_fma_f32 v42, -v40, v38, v36
	v_cmp_ge_f32_e64 s[0:1], 0, v42
	v_add_u32_e32 v42, 1, v38
	s_nop 0
	v_cndmask_b32_e64 v40, v38, v40, s[0:1]
	v_fma_f32 v38, -v42, v38, v36
	v_cmp_lt_f32_e64 s[0:1], 0, v38
	s_nop 1
	v_cndmask_b32_e64 v38, v40, v42, s[0:1]
	v_mul_f32_e32 v40, 0x37800000, v38
	v_cndmask_b32_e32 v38, v38, v40, vcc
	v_cmp_class_f32_e32 vcc, v36, v193
	s_nop 1
	v_cndmask_b32_e32 v36, v38, v36, vcc
	v_cmp_ngt_f32_e32 vcc, s18, v33
	s_nop 1
	v_cndmask_b32_e32 v33, 1.0, v36, vcc
	v_mul_f32_e32 v33, v34, v33
	s_waitcnt lgkmcnt(0)
	v_mul_f32_e32 v33, v56, v33
	ds_write_b32 v70, v35 offset:4608
	ds_write_b32 v70, v33 offset:41472
	v_add_f32_e32 v33, v59, v74
	v_mul_f32_e32 v33, 0xbfb8aa3b, v33
	v_exp_f32_e32 v33, v33
	v_add_f32_e32 v34, v43, v73
	v_mul_f32_e32 v34, 0xbfb8aa3b, v34
	v_exp_f32_e32 v34, v34
	v_add_f32_e32 v33, 1.0, v33
	v_rcp_f32_e32 v33, v33
	v_add_f32_e32 v34, 1.0, v34
	v_rcp_f32_e32 v34, v34
	v_mul_f32_e32 v33, v33, v72
	v_mul_f32_e32 v35, 0x3fb8aa3b, v33
	v_add_f32_e32 v33, v33, v33
	v_mul_f32_e32 v36, 0x3fb8aa3b, v33
	v_rndne_f32_e32 v36, v36
	v_fmamk_f32 v38, v36, 0xbf317218, v33
	v_fmac_f32_e32 v38, 0x3102e308, v36
	v_fmamk_f32 v40, v38, 0x395133b1, v192
	v_cmp_eq_f32_e32 vcc, s15, v36
	v_cvt_i32_f32_e32 v36, v36
	v_fmaak_f32 v40, v38, v40, 0x3c0887f9
	v_fmaak_f32 v40, v38, v40, 0x3d2aaa81
	v_fmaak_f32 v40, v38, v40, 0x3e2aaaab
	v_fma_f32 v40, v38, v40, 0.5
	v_ldexp_f32 v36, 1.0, v36
	v_mul_f32_e32 v40, v38, v40
	v_cndmask_b32_e32 v36, v36, v202, vcc
	v_fmac_f32_e32 v38, v38, v40
	v_add_f32_e32 v40, -1.0, v36
	v_fmac_f32_e32 v40, v36, v38
	v_add_f32_e32 v36, v40, v40
	v_cndmask_b32_e32 v36, v40, v36, vcc
	v_cmp_nlt_f32_e32 vcc, s16, v33
	v_exp_f32_e32 v35, v35
	s_nop 0
	v_cndmask_b32_e64 v36, v201, -v36, vcc
	v_cmp_gt_f32_e32 vcc, s17, v36
	v_mul_f32_e32 v38, 0x4f800000, v36
	s_nop 0
	v_cndmask_b32_e32 v36, v36, v38, vcc
	v_sqrt_f32_e32 v38, v36
	s_nop 0
	v_add_u32_e32 v40, -1, v38
	v_fma_f32 v42, -v40, v38, v36
	v_cmp_ge_f32_e64 s[0:1], 0, v42
	v_add_u32_e32 v42, 1, v38
	s_nop 0
	v_cndmask_b32_e64 v40, v38, v40, s[0:1]
	v_fma_f32 v38, -v42, v38, v36
	v_cmp_lt_f32_e64 s[0:1], 0, v38
	s_nop 1
	v_cndmask_b32_e64 v38, v40, v42, s[0:1]
	v_mul_f32_e32 v40, 0x37800000, v38
	ds_read2_b32 v[42:43], v32 offset0:192 offset1:224
	v_cndmask_b32_e32 v38, v38, v40, vcc
	v_cmp_class_f32_e32 vcc, v36, v193
	s_nop 1
	v_cndmask_b32_e32 v36, v38, v36, vcc
	v_cmp_ngt_f32_e32 vcc, s18, v33
	s_nop 1
	v_cndmask_b32_e32 v33, 1.0, v36, vcc
	v_mul_f32_e32 v33, v34, v33
	s_waitcnt lgkmcnt(0)
	v_mul_f32_e32 v32, v42, v33
	ds_write_b32 v70, v35 offset:4864
	ds_write_b32 v70, v32 offset:41728
	v_add_f32_e32 v32, v60, v74
	v_mul_f32_e32 v32, 0xbfb8aa3b, v32
	v_exp_f32_e32 v32, v32
	v_add_f32_e32 v33, v44, v73
	v_mul_f32_e32 v33, 0xbfb8aa3b, v33
	v_exp_f32_e32 v33, v33
	v_add_f32_e32 v32, 1.0, v32
	v_rcp_f32_e32 v32, v32
	v_add_f32_e32 v33, 1.0, v33
	v_rcp_f32_e32 v33, v33
	v_mul_f32_e32 v32, v32, v72
	v_mul_f32_e32 v34, 0x3fb8aa3b, v32
	v_add_f32_e32 v32, v32, v32
	v_mul_f32_e32 v35, 0x3fb8aa3b, v32
	v_rndne_f32_e32 v35, v35
	v_fmamk_f32 v36, v35, 0xbf317218, v32
	v_fmac_f32_e32 v36, 0x3102e308, v35
	v_fmamk_f32 v38, v36, 0x395133b1, v192
	v_cmp_eq_f32_e32 vcc, s15, v35
	v_cvt_i32_f32_e32 v35, v35
	v_fmaak_f32 v38, v36, v38, 0x3c0887f9
	v_fmaak_f32 v38, v36, v38, 0x3d2aaa81
	v_fmaak_f32 v38, v36, v38, 0x3e2aaaab
	v_fma_f32 v38, v36, v38, 0.5
	v_ldexp_f32 v35, 1.0, v35
	v_mul_f32_e32 v38, v36, v38
	v_cndmask_b32_e32 v35, v35, v202, vcc
	v_fmac_f32_e32 v36, v36, v38
	v_add_f32_e32 v38, -1.0, v35
	v_fmac_f32_e32 v38, v35, v36
	v_add_f32_e32 v35, v38, v38
	v_cndmask_b32_e32 v35, v38, v35, vcc
	v_cmp_nlt_f32_e32 vcc, s16, v32
	v_exp_f32_e32 v34, v34
	s_nop 0
	v_cndmask_b32_e64 v35, v201, -v35, vcc
	v_cmp_gt_f32_e32 vcc, s17, v35
	v_mul_f32_e32 v36, 0x4f800000, v35
	s_nop 0
	v_cndmask_b32_e32 v35, v35, v36, vcc
	v_sqrt_f32_e32 v36, v35
	s_nop 0
	v_add_u32_e32 v38, -1, v36
	v_fma_f32 v40, -v38, v36, v35
	v_cmp_ge_f32_e64 s[0:1], 0, v40
	v_add_u32_e32 v40, 1, v36
	s_nop 0
	v_cndmask_b32_e64 v38, v36, v38, s[0:1]
	v_fma_f32 v36, -v40, v36, v35
	v_cmp_lt_f32_e64 s[0:1], 0, v36
	s_nop 1
	v_cndmask_b32_e64 v36, v38, v40, s[0:1]
	v_mul_f32_e32 v38, 0x37800000, v36
	v_cndmask_b32_e32 v36, v36, v38, vcc
	v_cmp_class_f32_e32 vcc, v35, v193
	s_nop 1
	v_cndmask_b32_e32 v35, v36, v35, vcc
	v_cmp_ngt_f32_e32 vcc, s18, v32
	s_nop 1
	v_cndmask_b32_e32 v32, 1.0, v35, vcc
	v_mul_f32_e32 v32, v33, v32
	v_add_u32_e32 v33, 0xa800, v70
	ds_read2_b32 v[58:59], v33 offset1:32
	s_waitcnt lgkmcnt(0)
	v_mul_f32_e32 v32, v58, v32
	ds_write_b32 v70, v34 offset:6144
	ds_write_b32 v70, v32 offset:43008
	v_add_f32_e32 v32, v61, v74
	v_mul_f32_e32 v32, 0xbfb8aa3b, v32
	v_exp_f32_e32 v32, v32
	v_add_f32_e32 v34, v45, v73
	v_mul_f32_e32 v34, 0xbfb8aa3b, v34
	v_exp_f32_e32 v34, v34
	v_add_f32_e32 v32, 1.0, v32
	v_rcp_f32_e32 v32, v32
	ds_read2_b32 v[44:45], v33 offset0:64 offset1:96
	v_add_f32_e32 v34, 1.0, v34
	v_rcp_f32_e32 v34, v34
	v_mul_f32_e32 v32, v32, v72
	v_mul_f32_e32 v35, 0x3fb8aa3b, v32
	v_add_f32_e32 v32, v32, v32
	v_mul_f32_e32 v36, 0x3fb8aa3b, v32
	v_rndne_f32_e32 v36, v36
	v_fmamk_f32 v38, v36, 0xbf317218, v32
	v_fmac_f32_e32 v38, 0x3102e308, v36
	v_fmamk_f32 v40, v38, 0x395133b1, v192
	v_cmp_eq_f32_e32 vcc, s15, v36
	v_cvt_i32_f32_e32 v36, v36
	v_fmaak_f32 v40, v38, v40, 0x3c0887f9
	v_fmaak_f32 v40, v38, v40, 0x3d2aaa81
	v_fmaak_f32 v40, v38, v40, 0x3e2aaaab
	v_fma_f32 v40, v38, v40, 0.5
	v_ldexp_f32 v36, 1.0, v36
	v_mul_f32_e32 v40, v38, v40
	v_cndmask_b32_e32 v36, v36, v202, vcc
	v_fmac_f32_e32 v38, v38, v40
	v_add_f32_e32 v40, -1.0, v36
	v_fmac_f32_e32 v40, v36, v38
	v_add_f32_e32 v36, v40, v40
	v_cndmask_b32_e32 v36, v40, v36, vcc
	v_cmp_nlt_f32_e32 vcc, s16, v32
	v_exp_f32_e32 v35, v35
	s_nop 0
	v_cndmask_b32_e64 v36, v201, -v36, vcc
	v_cmp_gt_f32_e32 vcc, s17, v36
	v_mul_f32_e32 v38, 0x4f800000, v36
	s_nop 0
	v_cndmask_b32_e32 v36, v36, v38, vcc
	v_sqrt_f32_e32 v38, v36
	s_nop 0
	v_add_u32_e32 v40, -1, v38
	v_fma_f32 v42, -v40, v38, v36
	v_cmp_ge_f32_e64 s[0:1], 0, v42
	v_add_u32_e32 v42, 1, v38
	s_nop 0
	v_cndmask_b32_e64 v40, v38, v40, s[0:1]
	v_fma_f32 v38, -v42, v38, v36
	v_cmp_lt_f32_e64 s[0:1], 0, v38
	s_nop 1
	v_cndmask_b32_e64 v38, v40, v42, s[0:1]
	v_mul_f32_e32 v40, 0x37800000, v38
	v_cndmask_b32_e32 v38, v38, v40, vcc
	v_cmp_class_f32_e32 vcc, v36, v193
	s_nop 1
	v_cndmask_b32_e32 v36, v38, v36, vcc
	v_cmp_ngt_f32_e32 vcc, s18, v32
	s_nop 1
	v_cndmask_b32_e32 v32, 1.0, v36, vcc
	v_mul_f32_e32 v32, v34, v32
	s_waitcnt lgkmcnt(0)
	v_mul_f32_e32 v32, v44, v32
	ds_write_b32 v70, v35 offset:6400
	ds_write_b32 v70, v32 offset:43264
	v_add_f32_e32 v32, v62, v74
	v_mul_f32_e32 v32, 0xbfb8aa3b, v32
	v_exp_f32_e32 v32, v32
	v_add_f32_e32 v34, v46, v73
	v_mul_f32_e32 v34, 0xbfb8aa3b, v34
	v_exp_f32_e32 v34, v34
	v_add_f32_e32 v32, 1.0, v32
	v_rcp_f32_e32 v32, v32
	v_add_f32_e32 v34, 1.0, v34
	v_rcp_f32_e32 v34, v34
	v_mul_f32_e32 v32, v32, v72
	v_mul_f32_e32 v35, 0x3fb8aa3b, v32
	v_add_f32_e32 v32, v32, v32
	v_exp_f32_e32 v36, v35
	v_mul_f32_e32 v35, 0x3fb8aa3b, v32
	v_rndne_f32_e32 v35, v35
	v_fmamk_f32 v38, v35, 0xbf317218, v32
	v_fmac_f32_e32 v38, 0x3102e308, v35
	v_fmamk_f32 v40, v38, 0x395133b1, v192
	v_cmp_eq_f32_e32 vcc, s15, v35
	v_cvt_i32_f32_e32 v35, v35
	v_fmaak_f32 v40, v38, v40, 0x3c0887f9
	v_fmaak_f32 v40, v38, v40, 0x3d2aaa81
	v_fmaak_f32 v40, v38, v40, 0x3e2aaaab
	v_fma_f32 v40, v38, v40, 0.5
	v_ldexp_f32 v35, 1.0, v35
	v_mul_f32_e32 v40, v38, v40
	v_cndmask_b32_e32 v35, v35, v202, vcc
	v_fmac_f32_e32 v38, v38, v40
	v_add_f32_e32 v40, -1.0, v35
	v_fmac_f32_e32 v40, v35, v38
	v_add_f32_e32 v35, v40, v40
	v_cndmask_b32_e32 v35, v40, v35, vcc
	v_cmp_nlt_f32_e32 vcc, s16, v32
	s_nop 1
	v_cndmask_b32_e64 v35, v201, -v35, vcc
	v_cmp_gt_f32_e32 vcc, s17, v35
	v_mul_f32_e32 v38, 0x4f800000, v35
	s_nop 0
	v_cndmask_b32_e32 v35, v35, v38, vcc
	v_sqrt_f32_e32 v38, v35
	s_nop 0
	v_add_u32_e32 v40, -1, v38
	v_fma_f32 v42, -v40, v38, v35
	v_cmp_ge_f32_e64 s[0:1], 0, v42
	v_add_u32_e32 v42, 1, v38
	s_nop 0
	v_cndmask_b32_e64 v40, v38, v40, s[0:1]
	v_fma_f32 v38, -v42, v38, v35
	v_cmp_lt_f32_e64 s[0:1], 0, v38
	s_nop 1
	v_cndmask_b32_e64 v38, v40, v42, s[0:1]
	v_mul_f32_e32 v40, 0x37800000, v38
	v_cndmask_b32_e32 v38, v38, v40, vcc
	v_cmp_class_f32_e32 vcc, v35, v193
	s_nop 1
	v_cndmask_b32_e32 v35, v38, v35, vcc
	v_cmp_ngt_f32_e32 vcc, s18, v32
	s_nop 1
	v_cndmask_b32_e32 v32, 1.0, v35, vcc
	v_mul_f32_e32 v32, v34, v32
	ds_read2_b32 v[34:35], v33 offset0:128 offset1:160
	s_waitcnt lgkmcnt(0)
	v_mul_f32_e32 v32, v34, v32
	ds_write_b32 v70, v36 offset:6656
	ds_write_b32 v70, v32 offset:43520
	v_add_f32_e32 v32, v63, v74
	v_mul_f32_e32 v32, 0xbfb8aa3b, v32
	v_exp_f32_e32 v32, v32
	v_add_f32_e32 v34, v47, v73
	v_mul_f32_e32 v34, 0xbfb8aa3b, v34
	v_exp_f32_e32 v34, v34
	v_add_f32_e32 v32, 1.0, v32
	v_rcp_f32_e32 v32, v32
	v_lshlrev_b64 v[46:47], 2, v[96:97]
	v_add_f32_e32 v34, 1.0, v34
	v_rcp_f32_e32 v36, v34
	v_mul_f32_e32 v32, v32, v72
	v_mul_f32_e32 v34, 0x3fb8aa3b, v32
	v_add_f32_e32 v32, v32, v32
	v_mul_f32_e32 v38, 0x3fb8aa3b, v32
	v_rndne_f32_e32 v38, v38
	v_fmamk_f32 v40, v38, 0xbf317218, v32
	v_fmac_f32_e32 v40, 0x3102e308, v38
	v_fmamk_f32 v42, v40, 0x395133b1, v192
	v_cmp_eq_f32_e32 vcc, s15, v38
	v_cvt_i32_f32_e32 v38, v38
	v_fmaak_f32 v42, v40, v42, 0x3c0887f9
	v_fmaak_f32 v42, v40, v42, 0x3d2aaa81
	v_fmaak_f32 v42, v40, v42, 0x3e2aaaab
	v_fma_f32 v42, v40, v42, 0.5
	v_ldexp_f32 v38, 1.0, v38
	v_mul_f32_e32 v42, v40, v42
	v_cndmask_b32_e32 v38, v38, v202, vcc
	v_fmac_f32_e32 v40, v40, v42
	v_add_f32_e32 v42, -1.0, v38
	v_fmac_f32_e32 v42, v38, v40
	v_add_f32_e32 v38, v42, v42
	v_cndmask_b32_e32 v38, v42, v38, vcc
	v_cmp_nlt_f32_e32 vcc, s16, v32
	v_lshl_add_u64 v[60:61], s[10:11], 0, v[46:47]
	v_exp_f32_e32 v34, v34
	v_cndmask_b32_e64 v38, v201, -v38, vcc
	v_cmp_gt_f32_e32 vcc, s17, v38
	v_mul_f32_e32 v40, 0x4f800000, v38
	s_nop 0
	v_cndmask_b32_e32 v38, v38, v40, vcc
	v_sqrt_f32_e32 v40, v38
	s_nop 0
	v_add_u32_e32 v42, -1, v40
	v_fma_f32 v44, -v42, v40, v38
	v_cmp_ge_f32_e64 s[0:1], 0, v44
	v_add_u32_e32 v44, 1, v40
	s_nop 0
	v_cndmask_b32_e64 v42, v40, v42, s[0:1]
	v_fma_f32 v40, -v44, v40, v38
	v_cmp_lt_f32_e64 s[0:1], 0, v40
	s_nop 1
	v_cndmask_b32_e64 v40, v42, v44, s[0:1]
	v_mul_f32_e32 v42, 0x37800000, v40
	v_cndmask_b32_e32 v40, v40, v42, vcc
	v_cmp_class_f32_e32 vcc, v38, v193
	s_nop 1
	v_cndmask_b32_e32 v38, v40, v38, vcc
	v_cmp_ngt_f32_e32 vcc, s18, v32
	s_nop 1
	v_cndmask_b32_e32 v32, 1.0, v38, vcc
	v_mul_f32_e32 v36, v36, v32
	ds_read2_b32 v[32:33], v33 offset0:192 offset1:224
	s_waitcnt lgkmcnt(0)
	v_mul_f32_e32 v32, v32, v36
	ds_write_b32 v70, v32 offset:43776
	v_mov_b32_e32 v32, v226
	s_waitcnt vmcnt(0)
	v_mul_f32_e32 v32, 0xbfb8aa3b, v32
	v_exp_f32_e32 v32, v32
	s_nop 0
	v_add_f32_e32 v36, 1.0, v32
	v_add_f32_e32 v38, -1.0, v36
	v_sub_f32_e32 v40, v38, v36
	v_add_f32_e32 v40, 1.0, v40
	v_sub_f32_e32 v38, v32, v38
	v_add_f32_e32 v38, v38, v40
	v_frexp_mant_f32_e32 v40, v36
	v_cvt_f64_f32_e32 v[60:61], v36
	v_cmp_gt_f32_e32 vcc, s7, v40
	v_frexp_exp_i32_f64_e32 v40, v[60:61]
	s_nop 0
	v_subbrev_co_u32_e32 v40, vcc, 0, v40, vcc
	v_sub_u32_e32 v42, 0, v40
	v_ldexp_f32 v36, v36, v42
	v_ldexp_f32 v38, v38, v42
	v_add_f32_e32 v42, -1.0, v36
	v_add_f32_e32 v48, 1.0, v36
	v_add_f32_e32 v44, 1.0, v42
	v_add_f32_e32 v50, -1.0, v48
	v_sub_f32_e32 v44, v36, v44
	v_sub_f32_e32 v36, v36, v50
	v_add_f32_e32 v36, v38, v36
	v_add_f32_e32 v44, v38, v44
	v_add_f32_e32 v38, v48, v36
	v_sub_f32_e32 v48, v38, v48
	v_sub_f32_e32 v36, v36, v48
	v_rcp_f32_e32 v48, v38
	v_add_f32_e32 v61, v42, v44
	v_sub_f32_e32 v42, v61, v42
	v_sub_f32_e32 v42, v44, v42
	v_mul_f32_e32 v44, v61, v48
	v_mul_f32_e32 v62, v38, v44
	v_fma_f32 v72, v44, v38, -v62
	v_fmac_f32_e32 v72, v44, v36
	v_add_f32_e32 v60, v62, v72
	v_sub_f32_e32 v63, v61, v60
	v_pk_add_f32 v[74:75], v[60:61], v[62:63] neg_lo:[0,1] neg_hi:[0,1]
	v_mov_b32_e32 v73, v60
	v_pk_add_f32 v[60:61], v[74:75], v[72:73] neg_lo:[0,1] neg_hi:[0,1]
	v_cmp_neq_f32_e32 vcc, s40, v32
	v_add_f32_e32 v42, v42, v61
	v_add_f32_e32 v42, v60, v42
	v_add_f32_e32 v61, v63, v42
	v_mul_f32_e32 v50, v48, v61
	v_mul_f32_e32 v62, v38, v50
	v_fma_f32 v72, v50, v38, -v62
	v_fmac_f32_e32 v72, v50, v36
	v_add_f32_e32 v60, v62, v72
	v_sub_f32_e32 v36, v63, v61
	v_sub_f32_e32 v63, v61, v60
	v_pk_add_f32 v[74:75], v[60:61], v[62:63] neg_lo:[0,1] neg_hi:[0,1]
	v_mov_b32_e32 v73, v60
	v_add_f32_e32 v36, v42, v36
	v_pk_add_f32 v[60:61], v[74:75], v[72:73] neg_lo:[0,1] neg_hi:[0,1]
	v_add_f32_e32 v38, v44, v50
	v_add_f32_e32 v36, v36, v61
	v_add_f32_e32 v36, v60, v36
	v_add_f32_e32 v36, v63, v36
	v_sub_f32_e32 v42, v38, v44
	v_mul_f32_e32 v36, v48, v36
	v_sub_f32_e32 v42, v50, v42
	v_add_f32_e32 v36, v42, v36
	v_add_f32_e32 v42, v38, v36
	v_cvt_f32_i32_e32 v60, v40
	v_mul_f32_e32 v44, v42, v42
	v_fmamk_f32 v48, v44, 0x3e9b6dac, v191
	v_fmaak_f32 v169, v44, v48, 0x3f2aaada
	v_mul_f32_e32 v61, v42, v44
	v_pk_mul_f32 v[72:73], v[60:61], v[168:169]
	v_ldexp_f32 v63, v42, 1
	v_fma_f32 v62, v60, s39, -v72
	v_fmac_f32_e32 v62, 0xb102e308, v60
	v_sub_f32_e32 v38, v42, v38
	v_pk_add_f32 v[60:61], v[72:73], v[62:63]
	v_sub_f32_e32 v36, v36, v38
	v_sub_f32_e32 v38, v61, v63
	v_ldexp_f32 v36, v36, 1
	v_sub_f32_e32 v38, v73, v38
	v_add_f32_e32 v75, v36, v38
	v_mov_b32_e32 v74, v72
	v_pk_add_f32 v[72:73], v[60:61], v[72:73] neg_lo:[0,1] neg_hi:[0,1]
	v_pk_add_f32 v[76:77], v[60:61], v[74:75]
	v_mov_b32_e32 v63, v60
	v_mov_b32_e32 v73, v77
	v_pk_add_f32 v[78:79], v[62:63], v[72:73] neg_lo:[0,1] neg_hi:[0,1]
	v_pk_add_f32 v[62:63], v[62:63], v[72:73]
	v_mov_b32_e32 v74, v75
	v_pk_add_f32 v[72:73], v[62:63], v[60:61] op_sel:[1,0] op_sel_hi:[0,1] neg_lo:[0,1] neg_hi:[0,1]
	v_pk_add_f32 v[80:81], v[76:77], v[72:73] op_sel_hi:[1,0] neg_lo:[0,1] neg_hi:[0,1]
	v_mov_b32_e32 v76, v77
	v_mov_b32_e32 v77, v63
	v_pk_mov_b32 v[72:73], v[60:61], v[72:73] op_sel:[1,0]
	v_mov_b32_e32 v75, v60
	v_pk_add_f32 v[72:73], v[76:77], v[72:73] neg_lo:[0,1] neg_hi:[0,1]
	v_mov_b32_e32 v80, v78
	v_pk_add_f32 v[60:61], v[74:75], v[72:73] neg_lo:[0,1] neg_hi:[0,1]
	v_mov_b32_e32 v79, v63
	v_pk_add_f32 v[72:73], v[80:81], v[60:61]
	v_pk_add_f32 v[74:75], v[72:73], v[72:73] op_sel:[0,1] op_sel_hi:[1,0]
	v_pk_add_f32 v[62:63], v[62:63], v[74:75] op_sel:[1,0] op_sel_hi:[0,1]
	v_mov_b32_e32 v73, v62
	v_pk_add_f32 v[76:77], v[72:73], v[78:79] neg_lo:[0,1] neg_hi:[0,1]
	v_mov_b32_e32 v61, v74
	v_sub_f32_e32 v36, v72, v76
	v_pk_add_f32 v[60:61], v[60:61], v[76:77] neg_lo:[0,1] neg_hi:[0,1]
	v_sub_f32_e32 v36, v78, v36
	v_add_f32_e32 v36, v60, v36
	v_add_f32_e32 v36, v36, v61
	v_add_f32_e32 v36, v62, v36
	v_cndmask_b32_e32 v36, v199, v36, vcc
	v_cmp_ngt_f32_e32 vcc, -1.0, v32
	v_lshl_add_u64 v[60:61], s[24:25], 0, v[46:47]
	v_lshl_add_u64 v[46:47], s[8:9], 0, v[46:47]
	v_cndmask_b32_e32 v36, v200, v36, vcc
	v_cmp_neq_f32_e32 vcc, -1.0, v32
	v_mov_b32_e32 v38, v227
	s_waitcnt vmcnt(0)
	v_add_f32_e32 v0, v0, v38
	v_cndmask_b32_e32 v36, v201, v36, vcc
	v_cmp_lt_f32_e64 vcc, |v32|, s41
	v_mul_f32_e32 v0, 0xbfb8aa3b, v0
	v_exp_f32_e32 v0, v0
	v_cndmask_b32_e32 v32, v36, v32, vcc
	v_mov_b32_e32 v36, v228
	v_mul_f32_e32 v32, 0xc1000000, v32
	v_add_f32_e32 v0, 1.0, v0
	v_rcp_f32_e32 v0, v0
	v_add_f32_e32 v1, v1, v38
	v_mul_f32_e32 v1, 0xbfb8aa3b, v1
	v_exp_f32_e32 v1, v1
	s_waitcnt vmcnt(0)
	v_add_f32_e32 v16, v16, v36
	v_mul_f32_e32 v16, 0xbfb8aa3b, v16
	v_exp_f32_e32 v16, v16
	v_add_f32_e32 v1, 1.0, v1
	v_rcp_f32_e32 v1, v1
	v_add_f32_e32 v16, 1.0, v16
	v_rcp_f32_e32 v16, v16
	s_nop 0
	v_mul_f32_e32 v16, v16, v32
	v_mul_f32_e32 v40, 0x3fb8aa3b, v16
	v_add_f32_e32 v16, v16, v16
	v_mul_f32_e32 v42, 0x3fb8aa3b, v16
	v_rndne_f32_e32 v42, v42
	v_fmamk_f32 v44, v42, 0xbf317218, v16
	v_fmac_f32_e32 v44, 0x3102e308, v42
	v_fmamk_f32 v46, v44, 0x395133b1, v192
	v_cmp_eq_f32_e32 vcc, s15, v42
	v_cvt_i32_f32_e32 v42, v42
	v_fmaak_f32 v46, v44, v46, 0x3c0887f9
	v_fmaak_f32 v46, v44, v46, 0x3d2aaa81
	v_fmaak_f32 v46, v44, v46, 0x3e2aaaab
	v_fma_f32 v46, v44, v46, 0.5
	v_ldexp_f32 v42, 1.0, v42
	v_mul_f32_e32 v46, v44, v46
	v_cndmask_b32_e32 v42, v42, v202, vcc
	v_fmac_f32_e32 v44, v44, v46
	v_add_f32_e32 v46, -1.0, v42
	v_fmac_f32_e32 v46, v42, v44
	v_add_f32_e32 v42, v46, v46
	v_cndmask_b32_e32 v42, v46, v42, vcc
	v_cmp_nlt_f32_e32 vcc, s16, v16
	v_exp_f32_e32 v40, v40
	s_nop 0
	v_cndmask_b32_e64 v42, v201, -v42, vcc
	v_cmp_gt_f32_e32 vcc, s17, v42
	v_mul_f32_e32 v44, 0x4f800000, v42
	s_nop 0
	v_cndmask_b32_e32 v42, v42, v44, vcc
	v_sqrt_f32_e32 v44, v42
	s_nop 0
	v_add_u32_e32 v46, -1, v44
	v_fma_f32 v47, -v46, v44, v42
	v_cmp_ge_f32_e64 s[0:1], 0, v47
	v_add_u32_e32 v47, 1, v44
	s_nop 0
	v_cndmask_b32_e64 v46, v44, v46, s[0:1]
	v_fma_f32 v44, -v47, v44, v42
	v_cmp_lt_f32_e64 s[0:1], 0, v44
	s_nop 1
	v_cndmask_b32_e64 v44, v46, v47, s[0:1]
	v_mul_f32_e32 v46, 0x37800000, v44
	v_cndmask_b32_e32 v44, v44, v46, vcc
	v_cmp_class_f32_e32 vcc, v42, v193
	s_nop 1
	v_cndmask_b32_e32 v42, v44, v42, vcc
	v_cmp_ngt_f32_e32 vcc, s18, v16
	s_nop 1
	v_cndmask_b32_e32 v16, 1.0, v42, vcc
	v_mul_f32_e32 v0, v0, v16
	v_mul_f32_e32 v0, v65, v0
	ds_write_b32 v70, v40 offset:128
	ds_write_b32 v70, v0 offset:36992
	v_add_f32_e32 v0, v17, v36
	v_mul_f32_e32 v0, 0xbfb8aa3b, v0
	v_exp_f32_e32 v0, v0
	s_nop 0
	v_add_f32_e32 v0, 1.0, v0
	v_rcp_f32_e32 v0, v0
	s_nop 0
	v_mul_f32_e32 v0, v0, v32
	v_mul_f32_e32 v16, 0x3fb8aa3b, v0
	v_add_f32_e32 v0, v0, v0
	v_mul_f32_e32 v17, 0x3fb8aa3b, v0
	v_rndne_f32_e32 v17, v17
	v_fmamk_f32 v40, v17, 0xbf317218, v0
	v_fmac_f32_e32 v40, 0x3102e308, v17
	v_fmamk_f32 v42, v40, 0x395133b1, v192
	v_cmp_eq_f32_e32 vcc, s15, v17
	v_cvt_i32_f32_e32 v17, v17
	v_fmaak_f32 v42, v40, v42, 0x3c0887f9
	v_fmaak_f32 v42, v40, v42, 0x3d2aaa81
	v_fmaak_f32 v42, v40, v42, 0x3e2aaaab
	v_fma_f32 v42, v40, v42, 0.5
	v_ldexp_f32 v17, 1.0, v17
	v_mul_f32_e32 v42, v40, v42
	v_cndmask_b32_e32 v17, v17, v202, vcc
	v_fmac_f32_e32 v40, v40, v42
	v_add_f32_e32 v42, -1.0, v17
	v_fmac_f32_e32 v42, v17, v40
	v_add_f32_e32 v17, v42, v42
	v_cndmask_b32_e32 v17, v42, v17, vcc
	v_cmp_nlt_f32_e32 vcc, s16, v0
	v_exp_f32_e32 v16, v16
	s_nop 0
	v_cndmask_b32_e64 v17, v201, -v17, vcc
	v_cmp_gt_f32_e32 vcc, s17, v17
	v_mul_f32_e32 v40, 0x4f800000, v17
	s_nop 0
	v_cndmask_b32_e32 v17, v17, v40, vcc
	v_sqrt_f32_e32 v40, v17
	s_nop 0
	v_add_u32_e32 v42, -1, v40
	v_fma_f32 v44, -v42, v40, v17
	v_cmp_ge_f32_e64 s[0:1], 0, v44
	v_add_u32_e32 v44, 1, v40
	s_nop 0
	v_cndmask_b32_e64 v42, v40, v42, s[0:1]
	v_fma_f32 v40, -v44, v40, v17
	v_cmp_lt_f32_e64 s[0:1], 0, v40
	s_nop 1
	v_cndmask_b32_e64 v40, v42, v44, s[0:1]
	v_mul_f32_e32 v42, 0x37800000, v40
	v_cndmask_b32_e32 v40, v40, v42, vcc
	v_cmp_class_f32_e32 vcc, v17, v193
	s_nop 1
	v_cndmask_b32_e32 v17, v40, v17, vcc
	v_cmp_ngt_f32_e32 vcc, s18, v0
	s_nop 1
	v_cndmask_b32_e32 v0, 1.0, v17, vcc
	v_mul_f32_e32 v0, v1, v0
	v_mul_f32_e32 v0, v49, v0
	ds_write_b32 v70, v16 offset:384
	ds_write_b32 v70, v0 offset:37248
	v_add_f32_e32 v0, v18, v36
	v_mul_f32_e32 v0, 0xbfb8aa3b, v0
	v_exp_f32_e32 v0, v0
	v_add_f32_e32 v1, v2, v38
	v_mul_f32_e32 v1, 0xbfb8aa3b, v1
	v_exp_f32_e32 v1, v1
	v_add_f32_e32 v0, 1.0, v0
	v_rcp_f32_e32 v0, v0
	v_add_f32_e32 v1, 1.0, v1
	v_rcp_f32_e32 v1, v1
	v_mul_f32_e32 v0, v0, v32
	v_mul_f32_e32 v2, 0x3fb8aa3b, v0
	v_add_f32_e32 v0, v0, v0
	v_mul_f32_e32 v16, 0x3fb8aa3b, v0
	v_rndne_f32_e32 v16, v16
	v_fmamk_f32 v17, v16, 0xbf317218, v0
	v_fmac_f32_e32 v17, 0x3102e308, v16
	v_fmamk_f32 v18, v17, 0x395133b1, v192
	v_cmp_eq_f32_e32 vcc, s15, v16
	v_cvt_i32_f32_e32 v16, v16
	v_fmaak_f32 v18, v17, v18, 0x3c0887f9
	v_fmaak_f32 v18, v17, v18, 0x3d2aaa81
	v_fmaak_f32 v18, v17, v18, 0x3e2aaaab
	v_fma_f32 v18, v17, v18, 0.5
	v_ldexp_f32 v16, 1.0, v16
	v_mul_f32_e32 v18, v17, v18
	v_cndmask_b32_e32 v16, v16, v202, vcc
	v_fmac_f32_e32 v17, v17, v18
	v_add_f32_e32 v18, -1.0, v16
	v_fmac_f32_e32 v18, v16, v17
	v_add_f32_e32 v16, v18, v18
	v_cndmask_b32_e32 v16, v18, v16, vcc
	v_cmp_nlt_f32_e32 vcc, s16, v0
	v_exp_f32_e32 v2, v2
	s_nop 0
	v_cndmask_b32_e64 v16, v201, -v16, vcc
	v_cmp_gt_f32_e32 vcc, s17, v16
	v_mul_f32_e32 v17, 0x4f800000, v16
	s_nop 0
	v_cndmask_b32_e32 v16, v16, v17, vcc
	v_sqrt_f32_e32 v17, v16
	s_nop 0
	v_add_u32_e32 v18, -1, v17
	v_fma_f32 v40, -v18, v17, v16
	v_cmp_ge_f32_e64 s[0:1], 0, v40
	v_add_u32_e32 v40, 1, v17
	s_nop 0
	v_cndmask_b32_e64 v18, v17, v18, s[0:1]
	v_fma_f32 v17, -v40, v17, v16
	v_cmp_lt_f32_e64 s[0:1], 0, v17
	s_nop 1
	v_cndmask_b32_e64 v17, v18, v40, s[0:1]
	v_mul_f32_e32 v18, 0x37800000, v17
	v_cndmask_b32_e32 v17, v17, v18, vcc
	v_cmp_class_f32_e32 vcc, v16, v193
	s_nop 1
	v_cndmask_b32_e32 v16, v17, v16, vcc
	v_cmp_ngt_f32_e32 vcc, s18, v0
	s_nop 1
	v_cndmask_b32_e32 v0, 1.0, v16, vcc
	v_mul_f32_e32 v0, v1, v0
	v_mul_f32_e32 v0, v67, v0
	ds_write_b32 v70, v2 offset:640
	ds_write_b32 v70, v0 offset:37504
	v_add_f32_e32 v0, v19, v36
	v_mul_f32_e32 v0, 0xbfb8aa3b, v0
	v_exp_f32_e32 v0, v0
	v_add_f32_e32 v1, v3, v38
	v_mul_f32_e32 v1, 0xbfb8aa3b, v1
	v_exp_f32_e32 v1, v1
	v_add_f32_e32 v0, 1.0, v0
	v_rcp_f32_e32 v0, v0
	v_add_f32_e32 v1, 1.0, v1
	v_rcp_f32_e32 v1, v1
	v_mul_f32_e32 v0, v0, v32
	v_mul_f32_e32 v2, 0x3fb8aa3b, v0
	v_add_f32_e32 v0, v0, v0
	v_mul_f32_e32 v3, 0x3fb8aa3b, v0
	v_rndne_f32_e32 v3, v3
	v_fmamk_f32 v16, v3, 0xbf317218, v0
	v_fmac_f32_e32 v16, 0x3102e308, v3
	v_fmamk_f32 v17, v16, 0x395133b1, v192
	v_cmp_eq_f32_e32 vcc, s15, v3
	v_cvt_i32_f32_e32 v3, v3
	v_fmaak_f32 v17, v16, v17, 0x3c0887f9
	v_fmaak_f32 v17, v16, v17, 0x3d2aaa81
	v_fmaak_f32 v17, v16, v17, 0x3e2aaaab
	v_fma_f32 v17, v16, v17, 0.5
	v_ldexp_f32 v3, 1.0, v3
	v_mul_f32_e32 v17, v16, v17
	v_cndmask_b32_e32 v3, v3, v202, vcc
	v_fmac_f32_e32 v16, v16, v17
	v_add_f32_e32 v17, -1.0, v3
	v_fmac_f32_e32 v17, v3, v16
	v_add_f32_e32 v3, v17, v17
	v_cndmask_b32_e32 v3, v17, v3, vcc
	v_cmp_nlt_f32_e32 vcc, s16, v0
	v_exp_f32_e32 v2, v2
	s_nop 0
	v_cndmask_b32_e64 v3, v201, -v3, vcc
	v_cmp_gt_f32_e32 vcc, s17, v3
	v_mul_f32_e32 v16, 0x4f800000, v3
	s_nop 0
	v_cndmask_b32_e32 v3, v3, v16, vcc
	v_sqrt_f32_e32 v16, v3
	s_nop 0
	v_add_u32_e32 v17, -1, v16
	v_fma_f32 v18, -v17, v16, v3
	v_cmp_ge_f32_e64 s[0:1], 0, v18
	v_add_u32_e32 v18, 1, v16
	s_nop 0
	v_cndmask_b32_e64 v17, v16, v17, s[0:1]
	v_fma_f32 v16, -v18, v16, v3
	v_cmp_lt_f32_e64 s[0:1], 0, v16
	s_nop 1
	v_cndmask_b32_e64 v16, v17, v18, s[0:1]
	v_mul_f32_e32 v17, 0x37800000, v16
	v_cndmask_b32_e32 v16, v16, v17, vcc
	v_cmp_class_f32_e32 vcc, v3, v193
	s_nop 1
	v_cndmask_b32_e32 v3, v16, v3, vcc
	v_cmp_ngt_f32_e32 vcc, s18, v0
	s_nop 1
	v_cndmask_b32_e32 v0, 1.0, v3, vcc
	v_mul_f32_e32 v0, v1, v0
	v_mul_f32_e32 v0, v51, v0
	ds_write_b32 v70, v2 offset:896
	ds_write_b32 v70, v0 offset:37760
	v_add_f32_e32 v0, v20, v36
	v_mul_f32_e32 v0, 0xbfb8aa3b, v0
	v_exp_f32_e32 v0, v0
	v_add_f32_e32 v1, v4, v38
	v_mul_f32_e32 v1, 0xbfb8aa3b, v1
	v_exp_f32_e32 v1, v1
	v_add_f32_e32 v0, 1.0, v0
	v_rcp_f32_e32 v0, v0
	v_add_f32_e32 v1, 1.0, v1
	v_rcp_f32_e32 v1, v1
	v_mul_f32_e32 v0, v0, v32
	v_mul_f32_e32 v2, 0x3fb8aa3b, v0
	v_add_f32_e32 v0, v0, v0
	v_mul_f32_e32 v3, 0x3fb8aa3b, v0
	v_rndne_f32_e32 v3, v3
	v_fmamk_f32 v4, v3, 0xbf317218, v0
	v_fmac_f32_e32 v4, 0x3102e308, v3
	v_fmamk_f32 v16, v4, 0x395133b1, v192
	v_cmp_eq_f32_e32 vcc, s15, v3
	v_cvt_i32_f32_e32 v3, v3
	v_fmaak_f32 v16, v4, v16, 0x3c0887f9
	v_fmaak_f32 v16, v4, v16, 0x3d2aaa81
	v_fmaak_f32 v16, v4, v16, 0x3e2aaaab
	v_fma_f32 v16, v4, v16, 0.5
	v_ldexp_f32 v3, 1.0, v3
	v_mul_f32_e32 v16, v4, v16
	v_cndmask_b32_e32 v3, v3, v202, vcc
	v_fmac_f32_e32 v4, v4, v16
	v_add_f32_e32 v16, -1.0, v3
	v_fmac_f32_e32 v16, v3, v4
	v_add_f32_e32 v3, v16, v16
	v_cndmask_b32_e32 v3, v16, v3, vcc
	v_cmp_nlt_f32_e32 vcc, s16, v0
	v_exp_f32_e32 v2, v2
	s_nop 0
	v_cndmask_b32_e64 v3, v201, -v3, vcc
	v_cmp_gt_f32_e32 vcc, s17, v3
	v_mul_f32_e32 v4, 0x4f800000, v3
	s_nop 0
	v_cndmask_b32_e32 v3, v3, v4, vcc
	v_sqrt_f32_e32 v4, v3
	s_nop 0
	v_add_u32_e32 v16, -1, v4
	v_fma_f32 v17, -v16, v4, v3
	v_cmp_ge_f32_e64 s[0:1], 0, v17
	v_add_u32_e32 v17, 1, v4
	s_nop 0
	v_cndmask_b32_e64 v16, v4, v16, s[0:1]
	v_fma_f32 v4, -v17, v4, v3
	v_cmp_lt_f32_e64 s[0:1], 0, v4
	s_nop 1
	v_cndmask_b32_e64 v4, v16, v17, s[0:1]
	v_mul_f32_e32 v16, 0x37800000, v4
	v_cndmask_b32_e32 v4, v4, v16, vcc
	v_cmp_class_f32_e32 vcc, v3, v193
	s_nop 1
	v_cndmask_b32_e32 v3, v4, v3, vcc
	v_cmp_ngt_f32_e32 vcc, s18, v0
	s_nop 1
	v_cndmask_b32_e32 v0, 1.0, v3, vcc
	v_mul_f32_e32 v0, v1, v0
	v_mul_f32_e32 v0, v69, v0
	ds_write_b32 v70, v2 offset:2176
	ds_write_b32 v70, v0 offset:39040
	v_add_f32_e32 v0, v21, v36
	v_mul_f32_e32 v0, 0xbfb8aa3b, v0
	v_exp_f32_e32 v0, v0
	v_add_f32_e32 v1, v5, v38
	v_mul_f32_e32 v1, 0xbfb8aa3b, v1
	v_exp_f32_e32 v1, v1
	v_add_f32_e32 v0, 1.0, v0
	v_rcp_f32_e32 v0, v0
	v_add_f32_e32 v1, 1.0, v1
	v_rcp_f32_e32 v1, v1
	v_mul_f32_e32 v0, v0, v32
	v_mul_f32_e32 v2, 0x3fb8aa3b, v0
	v_add_f32_e32 v0, v0, v0
	v_mul_f32_e32 v3, 0x3fb8aa3b, v0
	v_rndne_f32_e32 v3, v3
	v_fmamk_f32 v4, v3, 0xbf317218, v0
	v_fmac_f32_e32 v4, 0x3102e308, v3
	v_fmamk_f32 v5, v4, 0x395133b1, v192
	v_cmp_eq_f32_e32 vcc, s15, v3
	v_cvt_i32_f32_e32 v3, v3
	v_fmaak_f32 v5, v4, v5, 0x3c0887f9
	v_fmaak_f32 v5, v4, v5, 0x3d2aaa81
	v_fmaak_f32 v5, v4, v5, 0x3e2aaaab
	v_fma_f32 v5, v4, v5, 0.5
	v_ldexp_f32 v3, 1.0, v3
	v_mul_f32_e32 v5, v4, v5
	v_cndmask_b32_e32 v3, v3, v202, vcc
	v_fmac_f32_e32 v4, v4, v5
	v_add_f32_e32 v5, -1.0, v3
	v_fmac_f32_e32 v5, v3, v4
	v_add_f32_e32 v3, v5, v5
	v_cndmask_b32_e32 v3, v5, v3, vcc
	v_cmp_nlt_f32_e32 vcc, s16, v0
	v_exp_f32_e32 v2, v2
	s_nop 0
	v_cndmask_b32_e64 v3, v201, -v3, vcc
	v_cmp_gt_f32_e32 vcc, s17, v3
	v_mul_f32_e32 v4, 0x4f800000, v3
	s_nop 0
	v_cndmask_b32_e32 v3, v3, v4, vcc
	v_sqrt_f32_e32 v4, v3
	s_nop 0
	v_add_u32_e32 v5, -1, v4
	v_fma_f32 v16, -v5, v4, v3
	v_cmp_ge_f32_e64 s[0:1], 0, v16
	v_add_u32_e32 v16, 1, v4
	s_nop 0
	v_cndmask_b32_e64 v5, v4, v5, s[0:1]
	v_fma_f32 v4, -v16, v4, v3
	v_cmp_lt_f32_e64 s[0:1], 0, v4
	s_nop 1
	v_cndmask_b32_e64 v4, v5, v16, s[0:1]
	v_mul_f32_e32 v5, 0x37800000, v4
	v_cndmask_b32_e32 v4, v4, v5, vcc
	v_cmp_class_f32_e32 vcc, v3, v193
	s_nop 1
	v_cndmask_b32_e32 v3, v4, v3, vcc
	v_cmp_ngt_f32_e32 vcc, s18, v0
	s_nop 1
	v_cndmask_b32_e32 v0, 1.0, v3, vcc
	v_mul_f32_e32 v0, v1, v0
	v_mul_f32_e32 v0, v37, v0
	ds_write_b32 v70, v2 offset:2432
	ds_write_b32 v70, v0 offset:39296
	v_add_f32_e32 v0, v22, v36
	v_mul_f32_e32 v0, 0xbfb8aa3b, v0
	v_exp_f32_e32 v0, v0
	v_add_f32_e32 v1, v6, v38
	v_mul_f32_e32 v1, 0xbfb8aa3b, v1
	v_exp_f32_e32 v1, v1
	v_add_f32_e32 v0, 1.0, v0
	v_rcp_f32_e32 v0, v0
	v_add_f32_e32 v1, 1.0, v1
	v_rcp_f32_e32 v1, v1
	v_mul_f32_e32 v0, v0, v32
	v_mul_f32_e32 v2, 0x3fb8aa3b, v0
	v_add_f32_e32 v0, v0, v0
	v_mul_f32_e32 v3, 0x3fb8aa3b, v0
	v_rndne_f32_e32 v3, v3
	v_fmamk_f32 v4, v3, 0xbf317218, v0
	v_fmac_f32_e32 v4, 0x3102e308, v3
	v_fmamk_f32 v5, v4, 0x395133b1, v192
	v_cmp_eq_f32_e32 vcc, s15, v3
	v_cvt_i32_f32_e32 v3, v3
	v_fmaak_f32 v5, v4, v5, 0x3c0887f9
	v_fmaak_f32 v5, v4, v5, 0x3d2aaa81
	v_fmaak_f32 v5, v4, v5, 0x3e2aaaab
	v_fma_f32 v5, v4, v5, 0.5
	v_ldexp_f32 v3, 1.0, v3
	v_mul_f32_e32 v5, v4, v5
	v_cndmask_b32_e32 v3, v3, v202, vcc
	v_fmac_f32_e32 v4, v4, v5
	v_add_f32_e32 v5, -1.0, v3
	v_fmac_f32_e32 v5, v3, v4
	v_add_f32_e32 v3, v5, v5
	v_cndmask_b32_e32 v3, v5, v3, vcc
	v_cmp_nlt_f32_e32 vcc, s16, v0
	v_exp_f32_e32 v2, v2
	s_nop 0
	v_cndmask_b32_e64 v3, v201, -v3, vcc
	v_cmp_gt_f32_e32 vcc, s17, v3
	v_mul_f32_e32 v4, 0x4f800000, v3
	s_nop 0
	v_cndmask_b32_e32 v3, v3, v4, vcc
	v_sqrt_f32_e32 v4, v3
	s_nop 0
	v_add_u32_e32 v5, -1, v4
	v_fma_f32 v6, -v5, v4, v3
	v_cmp_ge_f32_e64 s[0:1], 0, v6
	v_add_u32_e32 v6, 1, v4
	s_nop 0
	v_cndmask_b32_e64 v5, v4, v5, s[0:1]
	v_fma_f32 v4, -v6, v4, v3
	v_cmp_lt_f32_e64 s[0:1], 0, v4
	s_nop 1
	v_cndmask_b32_e64 v4, v5, v6, s[0:1]
	v_mul_f32_e32 v5, 0x37800000, v4
	v_cndmask_b32_e32 v4, v4, v5, vcc
	v_cmp_class_f32_e32 vcc, v3, v193
	s_nop 1
	v_cndmask_b32_e32 v3, v4, v3, vcc
	v_cmp_ngt_f32_e32 vcc, s18, v0
	s_nop 1
	v_cndmask_b32_e32 v0, 1.0, v3, vcc
	v_mul_f32_e32 v0, v1, v0
	v_mul_f32_e32 v0, v53, v0
	ds_write_b32 v70, v2 offset:2688
	ds_write_b32 v70, v0 offset:39552
	v_add_f32_e32 v0, v23, v36
	v_mul_f32_e32 v0, 0xbfb8aa3b, v0
	v_exp_f32_e32 v0, v0
	v_add_f32_e32 v1, v7, v38
	v_mul_f32_e32 v1, 0xbfb8aa3b, v1
	v_exp_f32_e32 v1, v1
	v_add_f32_e32 v0, 1.0, v0
	v_rcp_f32_e32 v0, v0
	v_add_f32_e32 v1, 1.0, v1
	v_rcp_f32_e32 v1, v1
	v_mul_f32_e32 v0, v0, v32
	v_mul_f32_e32 v2, 0x3fb8aa3b, v0
	v_add_f32_e32 v0, v0, v0
	v_mul_f32_e32 v3, 0x3fb8aa3b, v0
	v_rndne_f32_e32 v3, v3
	v_fmamk_f32 v4, v3, 0xbf317218, v0
	v_fmac_f32_e32 v4, 0x3102e308, v3
	v_fmamk_f32 v5, v4, 0x395133b1, v192
	v_cmp_eq_f32_e32 vcc, s15, v3
	v_cvt_i32_f32_e32 v3, v3
	v_fmaak_f32 v5, v4, v5, 0x3c0887f9
	v_fmaak_f32 v5, v4, v5, 0x3d2aaa81
	v_fmaak_f32 v5, v4, v5, 0x3e2aaaab
	v_fma_f32 v5, v4, v5, 0.5
	v_ldexp_f32 v3, 1.0, v3
	v_mul_f32_e32 v5, v4, v5
	v_cndmask_b32_e32 v3, v3, v202, vcc
	v_fmac_f32_e32 v4, v4, v5
	v_add_f32_e32 v5, -1.0, v3
	v_fmac_f32_e32 v5, v3, v4
	v_add_f32_e32 v3, v5, v5
	v_cndmask_b32_e32 v3, v5, v3, vcc
	v_cmp_nlt_f32_e32 vcc, s16, v0
	v_exp_f32_e32 v2, v2
	s_nop 0
	v_cndmask_b32_e64 v3, v201, -v3, vcc
	v_cmp_gt_f32_e32 vcc, s17, v3
	v_mul_f32_e32 v4, 0x4f800000, v3
	s_nop 0
	v_cndmask_b32_e32 v3, v3, v4, vcc
	v_sqrt_f32_e32 v4, v3
	s_nop 0
	v_add_u32_e32 v5, -1, v4
	v_fma_f32 v6, -v5, v4, v3
	v_cmp_ge_f32_e64 s[0:1], 0, v6
	v_add_u32_e32 v6, 1, v4
	s_nop 0
	v_cndmask_b32_e64 v5, v4, v5, s[0:1]
	v_fma_f32 v4, -v6, v4, v3
	v_cmp_lt_f32_e64 s[0:1], 0, v4
	s_nop 1
	v_cndmask_b32_e64 v4, v5, v6, s[0:1]
	v_mul_f32_e32 v5, 0x37800000, v4
	v_cndmask_b32_e32 v4, v4, v5, vcc
	v_cmp_class_f32_e32 vcc, v3, v193
	s_nop 1
	v_cndmask_b32_e32 v3, v4, v3, vcc
	v_cmp_ngt_f32_e32 vcc, s18, v0
	s_nop 1
	v_cndmask_b32_e32 v0, 1.0, v3, vcc
	v_mul_f32_e32 v0, v1, v0
	v_mul_f32_e32 v0, v39, v0
	ds_write_b32 v70, v2 offset:2944
	ds_write_b32 v70, v0 offset:39808
	v_add_f32_e32 v0, v24, v36
	v_mul_f32_e32 v0, 0xbfb8aa3b, v0
	v_exp_f32_e32 v0, v0
	v_add_f32_e32 v1, v8, v38
	v_mul_f32_e32 v1, 0xbfb8aa3b, v1
	v_exp_f32_e32 v1, v1
	v_add_f32_e32 v0, 1.0, v0
	v_rcp_f32_e32 v0, v0
	v_add_f32_e32 v1, 1.0, v1
	v_rcp_f32_e32 v1, v1
	v_mul_f32_e32 v0, v0, v32
	v_mul_f32_e32 v2, 0x3fb8aa3b, v0
	v_add_f32_e32 v0, v0, v0
	v_mul_f32_e32 v3, 0x3fb8aa3b, v0
	v_rndne_f32_e32 v3, v3
	v_fmamk_f32 v4, v3, 0xbf317218, v0
	v_fmac_f32_e32 v4, 0x3102e308, v3
	v_fmamk_f32 v5, v4, 0x395133b1, v192
	v_cmp_eq_f32_e32 vcc, s15, v3
	v_cvt_i32_f32_e32 v3, v3
	v_fmaak_f32 v5, v4, v5, 0x3c0887f9
	v_fmaak_f32 v5, v4, v5, 0x3d2aaa81
	v_fmaak_f32 v5, v4, v5, 0x3e2aaaab
	v_fma_f32 v5, v4, v5, 0.5
	v_ldexp_f32 v3, 1.0, v3
	v_mul_f32_e32 v5, v4, v5
	v_cndmask_b32_e32 v3, v3, v202, vcc
	v_fmac_f32_e32 v4, v4, v5
	v_add_f32_e32 v5, -1.0, v3
	v_fmac_f32_e32 v5, v3, v4
	v_add_f32_e32 v3, v5, v5
	v_cndmask_b32_e32 v3, v5, v3, vcc
	v_cmp_nlt_f32_e32 vcc, s16, v0
	v_exp_f32_e32 v2, v2
	s_nop 0
	v_cndmask_b32_e64 v3, v201, -v3, vcc
	v_cmp_gt_f32_e32 vcc, s17, v3
	v_mul_f32_e32 v4, 0x4f800000, v3
	s_nop 0
	v_cndmask_b32_e32 v3, v3, v4, vcc
	v_sqrt_f32_e32 v4, v3
	s_nop 0
	v_add_u32_e32 v5, -1, v4
	v_fma_f32 v6, -v5, v4, v3
	v_cmp_ge_f32_e64 s[0:1], 0, v6
	v_add_u32_e32 v6, 1, v4
	s_nop 0
	v_cndmask_b32_e64 v5, v4, v5, s[0:1]
	v_fma_f32 v4, -v6, v4, v3
	v_cmp_lt_f32_e64 s[0:1], 0, v4
	s_nop 1
	v_cndmask_b32_e64 v4, v5, v6, s[0:1]
	v_mul_f32_e32 v5, 0x37800000, v4
	v_cndmask_b32_e32 v4, v4, v5, vcc
	v_cmp_class_f32_e32 vcc, v3, v193
	s_nop 1
	v_cndmask_b32_e32 v3, v4, v3, vcc
	v_cmp_ngt_f32_e32 vcc, s18, v0
	s_nop 1
	v_cndmask_b32_e32 v0, 1.0, v3, vcc
	v_mul_f32_e32 v0, v1, v0
	v_mul_f32_e32 v0, v55, v0
	ds_write_b32 v70, v2 offset:4224
	ds_write_b32 v70, v0 offset:41088
	v_add_f32_e32 v0, v25, v36
	v_mul_f32_e32 v0, 0xbfb8aa3b, v0
	v_exp_f32_e32 v0, v0
	v_add_f32_e32 v1, v9, v38
	v_mul_f32_e32 v1, 0xbfb8aa3b, v1
	v_exp_f32_e32 v1, v1
	v_add_f32_e32 v0, 1.0, v0
	v_rcp_f32_e32 v0, v0
	v_add_f32_e32 v1, 1.0, v1
	v_rcp_f32_e32 v1, v1
	v_mul_f32_e32 v0, v0, v32
	v_mul_f32_e32 v2, 0x3fb8aa3b, v0
	v_add_f32_e32 v0, v0, v0
	v_mul_f32_e32 v3, 0x3fb8aa3b, v0
	v_rndne_f32_e32 v3, v3
	v_fmamk_f32 v4, v3, 0xbf317218, v0
	v_fmac_f32_e32 v4, 0x3102e308, v3
	v_fmamk_f32 v5, v4, 0x395133b1, v192
	v_cmp_eq_f32_e32 vcc, s15, v3
	v_cvt_i32_f32_e32 v3, v3
	v_fmaak_f32 v5, v4, v5, 0x3c0887f9
	v_fmaak_f32 v5, v4, v5, 0x3d2aaa81
	v_fmaak_f32 v5, v4, v5, 0x3e2aaaab
	v_fma_f32 v5, v4, v5, 0.5
	v_ldexp_f32 v3, 1.0, v3
	v_mul_f32_e32 v5, v4, v5
	v_cndmask_b32_e32 v3, v3, v202, vcc
	v_fmac_f32_e32 v4, v4, v5
	v_add_f32_e32 v5, -1.0, v3
	v_fmac_f32_e32 v5, v3, v4
	v_add_f32_e32 v3, v5, v5
	v_cndmask_b32_e32 v3, v5, v3, vcc
	v_cmp_nlt_f32_e32 vcc, s16, v0
	v_exp_f32_e32 v2, v2
	s_nop 0
	v_cndmask_b32_e64 v3, v201, -v3, vcc
	v_cmp_gt_f32_e32 vcc, s17, v3
	v_mul_f32_e32 v4, 0x4f800000, v3
	s_nop 0
	v_cndmask_b32_e32 v3, v3, v4, vcc
	v_sqrt_f32_e32 v4, v3
	s_nop 0
	v_add_u32_e32 v5, -1, v4
	v_fma_f32 v6, -v5, v4, v3
	v_cmp_ge_f32_e64 s[0:1], 0, v6
	v_add_u32_e32 v6, 1, v4
	s_nop 0
	v_cndmask_b32_e64 v5, v4, v5, s[0:1]
	v_fma_f32 v4, -v6, v4, v3
	v_cmp_lt_f32_e64 s[0:1], 0, v4
	s_nop 1
	v_cndmask_b32_e64 v4, v5, v6, s[0:1]
	v_mul_f32_e32 v5, 0x37800000, v4
	v_cndmask_b32_e32 v4, v4, v5, vcc
	v_cmp_class_f32_e32 vcc, v3, v193
	s_nop 1
	v_cndmask_b32_e32 v3, v4, v3, vcc
	v_cmp_ngt_f32_e32 vcc, s18, v0
	s_nop 1
	v_cndmask_b32_e32 v0, 1.0, v3, vcc
	v_mul_f32_e32 v0, v1, v0
	v_mul_f32_e32 v0, v41, v0
	ds_write_b32 v70, v2 offset:4480
	ds_write_b32 v70, v0 offset:41344
	v_add_f32_e32 v0, v26, v36
	v_mul_f32_e32 v0, 0xbfb8aa3b, v0
	v_exp_f32_e32 v0, v0
	v_add_f32_e32 v1, v10, v38
	v_mul_f32_e32 v1, 0xbfb8aa3b, v1
	v_exp_f32_e32 v1, v1
	v_add_f32_e32 v0, 1.0, v0
	v_rcp_f32_e32 v0, v0
	v_add_f32_e32 v1, 1.0, v1
	v_rcp_f32_e32 v1, v1
	v_mul_f32_e32 v0, v0, v32
	v_mul_f32_e32 v2, 0x3fb8aa3b, v0
	v_add_f32_e32 v0, v0, v0
	v_mul_f32_e32 v3, 0x3fb8aa3b, v0
	v_rndne_f32_e32 v3, v3
	v_fmamk_f32 v4, v3, 0xbf317218, v0
	v_fmac_f32_e32 v4, 0x3102e308, v3
	v_fmamk_f32 v5, v4, 0x395133b1, v192
	v_cmp_eq_f32_e32 vcc, s15, v3
	v_cvt_i32_f32_e32 v3, v3
	v_fmaak_f32 v5, v4, v5, 0x3c0887f9
	v_fmaak_f32 v5, v4, v5, 0x3d2aaa81
	v_fmaak_f32 v5, v4, v5, 0x3e2aaaab
	v_fma_f32 v5, v4, v5, 0.5
	v_ldexp_f32 v3, 1.0, v3
	v_mul_f32_e32 v5, v4, v5
	v_cndmask_b32_e32 v3, v3, v202, vcc
	v_fmac_f32_e32 v4, v4, v5
	v_add_f32_e32 v5, -1.0, v3
	v_fmac_f32_e32 v5, v3, v4
	v_add_f32_e32 v3, v5, v5
	v_cndmask_b32_e32 v3, v5, v3, vcc
	v_cmp_nlt_f32_e32 vcc, s16, v0
	v_exp_f32_e32 v2, v2
	s_nop 0
	v_cndmask_b32_e64 v3, v201, -v3, vcc
	v_cmp_gt_f32_e32 vcc, s17, v3
	v_mul_f32_e32 v4, 0x4f800000, v3
	s_nop 0
	v_cndmask_b32_e32 v3, v3, v4, vcc
	v_sqrt_f32_e32 v4, v3
	s_nop 0
	v_add_u32_e32 v5, -1, v4
	v_fma_f32 v6, -v5, v4, v3
	v_cmp_ge_f32_e64 s[0:1], 0, v6
	v_add_u32_e32 v6, 1, v4
	s_nop 0
	v_cndmask_b32_e64 v5, v4, v5, s[0:1]
	v_fma_f32 v4, -v6, v4, v3
	v_cmp_lt_f32_e64 s[0:1], 0, v4
	s_nop 1
	v_cndmask_b32_e64 v4, v5, v6, s[0:1]
	v_mul_f32_e32 v5, 0x37800000, v4
	v_cndmask_b32_e32 v4, v4, v5, vcc
	v_cmp_class_f32_e32 vcc, v3, v193
	s_nop 1
	v_cndmask_b32_e32 v3, v4, v3, vcc
	v_cmp_ngt_f32_e32 vcc, s18, v0
	s_nop 1
	v_cndmask_b32_e32 v0, 1.0, v3, vcc
	v_mul_f32_e32 v0, v1, v0
	v_mul_f32_e32 v0, v57, v0
	ds_write_b32 v70, v2 offset:4736
	ds_write_b32 v70, v0 offset:41600
	v_add_f32_e32 v0, v27, v36
	v_mul_f32_e32 v0, 0xbfb8aa3b, v0
	v_exp_f32_e32 v0, v0
	v_add_f32_e32 v1, v11, v38
	v_mul_f32_e32 v1, 0xbfb8aa3b, v1
	v_exp_f32_e32 v1, v1
	v_add_f32_e32 v0, 1.0, v0
	v_rcp_f32_e32 v0, v0
	v_add_f32_e32 v1, 1.0, v1
	v_rcp_f32_e32 v1, v1
	v_mul_f32_e32 v0, v0, v32
	v_mul_f32_e32 v2, 0x3fb8aa3b, v0
	v_add_f32_e32 v0, v0, v0
	v_mul_f32_e32 v3, 0x3fb8aa3b, v0
	v_rndne_f32_e32 v3, v3
	v_fmamk_f32 v4, v3, 0xbf317218, v0
	v_fmac_f32_e32 v4, 0x3102e308, v3
	v_fmamk_f32 v5, v4, 0x395133b1, v192
	v_cmp_eq_f32_e32 vcc, s15, v3
	v_cvt_i32_f32_e32 v3, v3
	v_fmaak_f32 v5, v4, v5, 0x3c0887f9
	v_fmaak_f32 v5, v4, v5, 0x3d2aaa81
	v_fmaak_f32 v5, v4, v5, 0x3e2aaaab
	v_fma_f32 v5, v4, v5, 0.5
	v_ldexp_f32 v3, 1.0, v3
	v_mul_f32_e32 v5, v4, v5
	v_cndmask_b32_e32 v3, v3, v202, vcc
	v_fmac_f32_e32 v4, v4, v5
	v_add_f32_e32 v5, -1.0, v3
	v_fmac_f32_e32 v5, v3, v4
	v_add_f32_e32 v3, v5, v5
	v_cndmask_b32_e32 v3, v5, v3, vcc
	v_cmp_nlt_f32_e32 vcc, s16, v0
	v_exp_f32_e32 v2, v2
	s_nop 0
	v_cndmask_b32_e64 v3, v201, -v3, vcc
	v_cmp_gt_f32_e32 vcc, s17, v3
	v_mul_f32_e32 v4, 0x4f800000, v3
	s_nop 0
	v_cndmask_b32_e32 v3, v3, v4, vcc
	v_sqrt_f32_e32 v4, v3
	s_nop 0
	v_add_u32_e32 v5, -1, v4
	v_fma_f32 v6, -v5, v4, v3
	v_cmp_ge_f32_e64 s[0:1], 0, v6
	v_add_u32_e32 v6, 1, v4
	s_nop 0
	v_cndmask_b32_e64 v5, v4, v5, s[0:1]
	v_fma_f32 v4, -v6, v4, v3
	v_cmp_lt_f32_e64 s[0:1], 0, v4
	s_nop 1
	v_cndmask_b32_e64 v4, v5, v6, s[0:1]
	v_mul_f32_e32 v5, 0x37800000, v4
	v_cndmask_b32_e32 v4, v4, v5, vcc
	v_cmp_class_f32_e32 vcc, v3, v193
	s_nop 1
	v_cndmask_b32_e32 v3, v4, v3, vcc
	v_cmp_ngt_f32_e32 vcc, s18, v0
	s_nop 1
	v_cndmask_b32_e32 v0, 1.0, v3, vcc
	v_mul_f32_e32 v0, v1, v0
	v_mul_f32_e32 v0, v43, v0
	ds_write_b32 v70, v2 offset:4992
	ds_write_b32 v70, v0 offset:41856
	v_add_f32_e32 v0, v28, v36
	v_mul_f32_e32 v0, 0xbfb8aa3b, v0
	v_exp_f32_e32 v0, v0
	v_add_f32_e32 v1, v12, v38
	v_mul_f32_e32 v1, 0xbfb8aa3b, v1
	v_exp_f32_e32 v1, v1
	v_add_f32_e32 v0, 1.0, v0
	v_rcp_f32_e32 v0, v0
	v_add_f32_e32 v1, 1.0, v1
	v_rcp_f32_e32 v1, v1
	v_mul_f32_e32 v0, v0, v32
	v_mul_f32_e32 v2, 0x3fb8aa3b, v0
	v_add_f32_e32 v0, v0, v0
	v_mul_f32_e32 v3, 0x3fb8aa3b, v0
	v_rndne_f32_e32 v3, v3
	v_fmamk_f32 v4, v3, 0xbf317218, v0
	v_fmac_f32_e32 v4, 0x3102e308, v3
	v_fmamk_f32 v5, v4, 0x395133b1, v192
	v_cmp_eq_f32_e32 vcc, s15, v3
	v_cvt_i32_f32_e32 v3, v3
	v_fmaak_f32 v5, v4, v5, 0x3c0887f9
	v_fmaak_f32 v5, v4, v5, 0x3d2aaa81
	v_fmaak_f32 v5, v4, v5, 0x3e2aaaab
	v_fma_f32 v5, v4, v5, 0.5
	v_ldexp_f32 v3, 1.0, v3
	v_mul_f32_e32 v5, v4, v5
	v_cndmask_b32_e32 v3, v3, v202, vcc
	v_fmac_f32_e32 v4, v4, v5
	v_add_f32_e32 v5, -1.0, v3
	v_fmac_f32_e32 v5, v3, v4
	v_add_f32_e32 v3, v5, v5
	v_cndmask_b32_e32 v3, v5, v3, vcc
	v_cmp_nlt_f32_e32 vcc, s16, v0
	v_exp_f32_e32 v2, v2
	s_nop 0
	v_cndmask_b32_e64 v3, v201, -v3, vcc
	v_cmp_gt_f32_e32 vcc, s17, v3
	v_mul_f32_e32 v4, 0x4f800000, v3
	s_nop 0
	v_cndmask_b32_e32 v3, v3, v4, vcc
	v_sqrt_f32_e32 v4, v3
	s_nop 0
	v_add_u32_e32 v5, -1, v4
	v_fma_f32 v6, -v5, v4, v3
	v_cmp_ge_f32_e64 s[0:1], 0, v6
	v_add_u32_e32 v6, 1, v4
	s_nop 0
	v_cndmask_b32_e64 v5, v4, v5, s[0:1]
	v_fma_f32 v4, -v6, v4, v3
	v_cmp_lt_f32_e64 s[0:1], 0, v4
	s_nop 1
	v_cndmask_b32_e64 v4, v5, v6, s[0:1]
	v_mul_f32_e32 v5, 0x37800000, v4
	v_cndmask_b32_e32 v4, v4, v5, vcc
	v_cmp_class_f32_e32 vcc, v3, v193
	s_nop 1
	v_cndmask_b32_e32 v3, v4, v3, vcc
	v_cmp_ngt_f32_e32 vcc, s18, v0
	s_nop 1
	v_cndmask_b32_e32 v0, 1.0, v3, vcc
	v_mul_f32_e32 v0, v1, v0
	v_mul_f32_e32 v0, v59, v0
	ds_write_b32 v70, v2 offset:6272
	ds_write_b32 v70, v0 offset:43136
	v_add_f32_e32 v0, v29, v36
	v_mul_f32_e32 v0, 0xbfb8aa3b, v0
	v_exp_f32_e32 v0, v0
	v_add_f32_e32 v1, v13, v38
	v_mul_f32_e32 v1, 0xbfb8aa3b, v1
	v_exp_f32_e32 v1, v1
	v_add_f32_e32 v0, 1.0, v0
	v_rcp_f32_e32 v0, v0
	v_add_f32_e32 v1, 1.0, v1
	v_rcp_f32_e32 v1, v1
	v_mul_f32_e32 v0, v0, v32
	v_mul_f32_e32 v2, 0x3fb8aa3b, v0
	v_add_f32_e32 v0, v0, v0
	v_mul_f32_e32 v3, 0x3fb8aa3b, v0
	v_rndne_f32_e32 v3, v3
	v_fmamk_f32 v4, v3, 0xbf317218, v0
	v_fmac_f32_e32 v4, 0x3102e308, v3
	v_fmamk_f32 v5, v4, 0x395133b1, v192
	v_cmp_eq_f32_e32 vcc, s15, v3
	v_cvt_i32_f32_e32 v3, v3
	v_fmaak_f32 v5, v4, v5, 0x3c0887f9
	v_fmaak_f32 v5, v4, v5, 0x3d2aaa81
	v_fmaak_f32 v5, v4, v5, 0x3e2aaaab
	v_fma_f32 v5, v4, v5, 0.5
	v_ldexp_f32 v3, 1.0, v3
	v_mul_f32_e32 v5, v4, v5
	v_cndmask_b32_e32 v3, v3, v202, vcc
	v_fmac_f32_e32 v4, v4, v5
	v_add_f32_e32 v5, -1.0, v3
	v_fmac_f32_e32 v5, v3, v4
	v_add_f32_e32 v3, v5, v5
	v_cndmask_b32_e32 v3, v5, v3, vcc
	v_cmp_nlt_f32_e32 vcc, s16, v0
	v_exp_f32_e32 v2, v2
	s_nop 0
	v_cndmask_b32_e64 v3, v201, -v3, vcc
	v_cmp_gt_f32_e32 vcc, s17, v3
	v_mul_f32_e32 v4, 0x4f800000, v3
	s_nop 0
	v_cndmask_b32_e32 v3, v3, v4, vcc
	v_sqrt_f32_e32 v4, v3
	s_nop 0
	v_add_u32_e32 v5, -1, v4
	v_fma_f32 v6, -v5, v4, v3
	v_cmp_ge_f32_e64 s[0:1], 0, v6
	v_add_u32_e32 v6, 1, v4
	s_nop 0
	v_cndmask_b32_e64 v5, v4, v5, s[0:1]
	v_fma_f32 v4, -v6, v4, v3
	v_cmp_lt_f32_e64 s[0:1], 0, v4
	s_nop 1
	v_cndmask_b32_e64 v4, v5, v6, s[0:1]
	v_mul_f32_e32 v5, 0x37800000, v4
	v_cndmask_b32_e32 v4, v4, v5, vcc
	v_cmp_class_f32_e32 vcc, v3, v193
	s_nop 1
	v_cndmask_b32_e32 v3, v4, v3, vcc
	v_cmp_ngt_f32_e32 vcc, s18, v0
	s_nop 1
	v_cndmask_b32_e32 v0, 1.0, v3, vcc
	v_mul_f32_e32 v0, v1, v0
	v_mul_f32_e32 v0, v45, v0
	ds_write_b32 v70, v2 offset:6528
	ds_write_b32 v70, v0 offset:43392
	v_add_f32_e32 v0, v30, v36
	v_mul_f32_e32 v0, 0xbfb8aa3b, v0
	v_exp_f32_e32 v0, v0
	v_add_f32_e32 v1, v14, v38
	v_mul_f32_e32 v1, 0xbfb8aa3b, v1
	v_exp_f32_e32 v1, v1
	v_add_f32_e32 v0, 1.0, v0
	v_rcp_f32_e32 v0, v0
	v_add_f32_e32 v1, 1.0, v1
	v_rcp_f32_e32 v1, v1
	v_mul_f32_e32 v0, v0, v32
	v_mul_f32_e32 v2, 0x3fb8aa3b, v0
	v_add_f32_e32 v0, v0, v0
	v_mul_f32_e32 v3, 0x3fb8aa3b, v0
	v_rndne_f32_e32 v3, v3
	v_fmamk_f32 v4, v3, 0xbf317218, v0
	v_fmac_f32_e32 v4, 0x3102e308, v3
	v_fmamk_f32 v5, v4, 0x395133b1, v192
	v_cmp_eq_f32_e32 vcc, s15, v3
	v_cvt_i32_f32_e32 v3, v3
	v_fmaak_f32 v5, v4, v5, 0x3c0887f9
	v_fmaak_f32 v5, v4, v5, 0x3d2aaa81
	v_fmaak_f32 v5, v4, v5, 0x3e2aaaab
	v_fma_f32 v5, v4, v5, 0.5
	v_ldexp_f32 v3, 1.0, v3
	v_mul_f32_e32 v5, v4, v5
	v_cndmask_b32_e32 v3, v3, v202, vcc
	v_fmac_f32_e32 v4, v4, v5
	v_add_f32_e32 v5, -1.0, v3
	v_fmac_f32_e32 v5, v3, v4
	v_add_f32_e32 v3, v5, v5
	v_cndmask_b32_e32 v3, v5, v3, vcc
	v_cmp_nlt_f32_e32 vcc, s16, v0
	v_exp_f32_e32 v2, v2
	s_nop 0
	v_cndmask_b32_e64 v3, v201, -v3, vcc
	v_cmp_gt_f32_e32 vcc, s17, v3
	v_mul_f32_e32 v4, 0x4f800000, v3
	s_nop 0
	v_cndmask_b32_e32 v3, v3, v4, vcc
	v_sqrt_f32_e32 v4, v3
	s_nop 0
	v_add_u32_e32 v5, -1, v4
	v_fma_f32 v6, -v5, v4, v3
	v_cmp_ge_f32_e64 s[0:1], 0, v6
	v_add_u32_e32 v6, 1, v4
	s_nop 0
	v_cndmask_b32_e64 v5, v4, v5, s[0:1]
	v_fma_f32 v4, -v6, v4, v3
	v_cmp_lt_f32_e64 s[0:1], 0, v4
	s_nop 1
	v_cndmask_b32_e64 v4, v5, v6, s[0:1]
	v_mul_f32_e32 v5, 0x37800000, v4
	v_cndmask_b32_e32 v4, v4, v5, vcc
	v_cmp_class_f32_e32 vcc, v3, v193
	s_nop 1
	v_cndmask_b32_e32 v3, v4, v3, vcc
	v_cmp_ngt_f32_e32 vcc, s18, v0
	s_nop 1
	v_cndmask_b32_e32 v0, 1.0, v3, vcc
	v_mul_f32_e32 v0, v1, v0
	v_mul_f32_e32 v0, v35, v0
	v_add_u32_e32 v1, 0x1800, v70
	ds_write2_b32 v1, v2, v34 offset0:160 offset1:192
	ds_write_b32 v70, v0 offset:43648
	v_add_f32_e32 v0, v31, v36
	v_mul_f32_e32 v0, 0xbfb8aa3b, v0
	v_exp_f32_e32 v0, v0
	v_add_f32_e32 v1, v15, v38
	v_mul_f32_e32 v1, 0xbfb8aa3b, v1
	v_exp_f32_e32 v1, v1
	v_add_f32_e32 v0, 1.0, v0
	v_rcp_f32_e32 v0, v0
	v_add_f32_e32 v1, 1.0, v1
	v_rcp_f32_e32 v1, v1
	v_mul_f32_e32 v0, v0, v32
	v_mul_f32_e32 v2, 0x3fb8aa3b, v0
	v_add_f32_e32 v0, v0, v0
	v_mul_f32_e32 v3, 0x3fb8aa3b, v0
	v_rndne_f32_e32 v3, v3
	v_fmamk_f32 v4, v3, 0xbf317218, v0
	v_fmac_f32_e32 v4, 0x3102e308, v3
	v_fmamk_f32 v5, v4, 0x395133b1, v192
	v_cmp_eq_f32_e32 vcc, s15, v3
	v_cvt_i32_f32_e32 v3, v3
	v_fmaak_f32 v5, v4, v5, 0x3c0887f9
	v_fmaak_f32 v5, v4, v5, 0x3d2aaa81
	v_fmaak_f32 v5, v4, v5, 0x3e2aaaab
	v_fma_f32 v5, v4, v5, 0.5
	v_ldexp_f32 v3, 1.0, v3
	v_mul_f32_e32 v5, v4, v5
	v_cndmask_b32_e32 v3, v3, v202, vcc
	v_fmac_f32_e32 v4, v4, v5
	v_add_f32_e32 v5, -1.0, v3
	v_fmac_f32_e32 v5, v3, v4
	v_add_f32_e32 v3, v5, v5
	v_cndmask_b32_e32 v3, v5, v3, vcc
	v_cmp_nlt_f32_e32 vcc, s16, v0
	v_exp_f32_e32 v2, v2
	s_nop 0
	v_cndmask_b32_e64 v3, v201, -v3, vcc
	v_cmp_gt_f32_e32 vcc, s17, v3
	v_mul_f32_e32 v4, 0x4f800000, v3
	s_nop 0
	v_cndmask_b32_e32 v3, v3, v4, vcc
	v_sqrt_f32_e32 v4, v3
	s_nop 0
	v_add_u32_e32 v5, -1, v4
	v_fma_f32 v6, -v5, v4, v3
	v_cmp_ge_f32_e64 s[0:1], 0, v6
	v_add_u32_e32 v6, 1, v4
	s_nop 0
	v_cndmask_b32_e64 v5, v4, v5, s[0:1]
	v_fma_f32 v4, -v6, v4, v3
	v_cmp_lt_f32_e64 s[0:1], 0, v4
	s_nop 1
	v_cndmask_b32_e64 v4, v5, v6, s[0:1]
	v_mul_f32_e32 v5, 0x37800000, v4
	v_cndmask_b32_e32 v4, v4, v5, vcc
	v_cmp_class_f32_e32 vcc, v3, v193
	v_mov_b32_e32 v6, 1.0
	s_mov_b32 s0, 24
	v_cndmask_b32_e32 v3, v4, v3, vcc
	v_cmp_ngt_f32_e32 vcc, s18, v0
	s_nop 1
	v_cndmask_b32_e32 v0, 1.0, v3, vcc
	v_mul_f32_e32 v0, v1, v0
	v_mul_f32_e32 v0, v33, v0
	ds_write_b32 v70, v2 offset:7040
	ds_write_b32 v70, v0 offset:43904
	v_mov_b32_e32 v2, v162
	s_waitcnt lgkmcnt(0)
	s_barrier
	s_cselect_b64 vcc, -1, 0
	v_and_b32_e32 v3, 63, v2
	v_ashrrev_i32_e32 v4, 6, v2
	v_lshl_or_b32 v5, v4, 11, v3
	v_mov_b32_e32 v1, 0

.LBB0_587:
	s_mul_hi_i32 s0, s2, 0x38e38e39
	s_lshr_b32 s1, s0, 31
	s_ashr_i32 s0, s0, 2
	s_add_i32 s0, s0, s1
	s_mul_i32 s1, s0, 18
	s_sub_i32 s1, s2, s1
	s_and_b32 s13, s0, 1
	s_bfe_u32 s3, s0, 0x20001
	s_ashr_i32 s0, s0, 3
	s_lshl_b32 s4, s1, 7
	s_cmp_lt_i32 s1, 2
	s_movk_i32 s6, 0xff00
	s_cselect_b32 s1, 8, 11
	s_cselect_b32 s6, 0x4000, s6
	s_lshl_b32 s0, s0, s1
	s_add_i32 s12, s6, s4
	s_waitcnt vmcnt(7)
	v_mov_b32_e32 v65, v162
	s_add_i32 s12, s12, s0
	s_movk_i32 s0, 0x80
	v_cmp_gt_i32_e32 vcc, s0, v65
	v_lshl_add_u32 v2, v65, 2, 0
	s_barrier
	s_and_saveexec_b64 s[6:7], vcc
	s_cbranch_execz .LBB0_589
	s_waitcnt lgkmcnt(0)
	v_add_u32_e32 v0, s12, v65
	v_ashrrev_i32_e32 v1, 31, v0
	v_readlane_b32 s0, v249, 17
	v_lshlrev_b64 v[0:1], 6, v[0:1]
	v_readlane_b32 s1, v249, 18
	s_lshl_b32 s38, s13, 3
	s_lshl_b32 s4, s13, 5
	v_lshl_add_u64 v[0:1], s[0:1], 0, v[0:1]
	v_readlane_b32 s8, v248, 19
	v_lshl_add_u64 v[0:1], v[0:1], 0, s[4:5]
	s_lshl_b32 s4, s3, 2
	s_or_b32 s0, s38, s8
	v_lshl_add_u64 v[0:1], v[0:1], 0, s[4:5]
	s_or_b32 s4, s0, s3
	v_readlane_b32 s16, v251, 20
	s_lshl_b64 s[0:1], s[4:5], 2
	v_readlane_b32 s20, v251, 24
	v_readlane_b32 s21, v251, 25
	s_add_u32 s0, s20, s0
	s_addc_u32 s1, s21, s1
	global_load_dword v4, v97, s[0:1]
	s_or_b32 s0, s3, s8
	s_add_i32 s4, s0, s38
	s_lshl_b64 s[0:1], s[4:5], 2
	s_add_u32 s0, s20, s0
	s_addc_u32 s1, s21, s1
	global_load_dword v3, v[0:1], off
	v_readlane_b32 s30, v251, 34
	global_load_dword v0, v[0:1], off offset:16
	v_readlane_b32 s31, v251, 35
	global_load_dword v1, v97, s[0:1] offset:16
	s_mov_b32 s0, 0xbfb8aa3b
	v_readlane_b32 s17, v251, 21
	v_readlane_b32 s18, v251, 22
	v_readlane_b32 s19, v251, 23
	v_readlane_b32 s22, v251, 26
	v_readlane_b32 s23, v251, 27
	v_readlane_b32 s24, v251, 28
	v_readlane_b32 s25, v251, 29
	v_readlane_b32 s27, v251, 31
	v_readlane_b32 s28, v251, 32
	v_readlane_b32 s29, v251, 33
	v_readlane_b32 s30, v248, 2
	s_mov_b32 s24, s69
	s_mov_b32 s27, s68
	s_mov_b64 s[16:17], s[82:83]
	s_mov_b32 s25, 0x85000
	s_mov_b32 s23, 0x59000
	s_mov_b32 s22, 0x2d000
	s_mov_b32 s19, 0x2c000
	s_movk_i32 s18, 0x1600
	s_movk_i32 s29, 0x47ff
	s_mov_b32 s28, 0x4800000
	v_readlane_b32 s31, v248, 3
	s_mov_b32 s20, 0x58000
	s_mov_b32 s21, 0x84000
	v_readlane_b32 s26, v251, 30
	s_waitcnt vmcnt(2)
	v_add_f32_e32 v3, v3, v4
	v_add_u32_e32 v4, 0x11000, v2
	ds_write_b32 v4, v3
	s_waitcnt vmcnt(0)
	v_add_f32_e32 v1, v0, v1
	v_min_f32_e32 v0, 0, v1
	v_mul_f32_e64 v1, |v1|, s0
	v_exp_f32_e32 v1, v1
	s_mov_b32 s0, 0x3f2aaaab
	v_add_f32_e32 v3, 1.0, v1
	v_add_f32_e32 v4, -1.0, v3
	v_sub_f32_e32 v5, v4, v3
	v_add_f32_e32 v5, 1.0, v5
	v_sub_f32_e32 v4, v1, v4
	v_add_f32_e32 v6, v4, v5
	v_frexp_mant_f32_e32 v4, v3
	v_cmp_gt_f32_e64 s[0:1], s0, v4
	v_cvt_f64_f32_e32 v[4:5], v3
	v_frexp_exp_i32_f64_e32 v4, v[4:5]
	v_subbrev_co_u32_e64 v4, s[0:1], 0, v4, s[0:1]
	v_sub_u32_e32 v5, 0, v4
	v_ldexp_f32 v3, v3, v5
	v_ldexp_f32 v5, v6, v5
	v_add_f32_e32 v6, -1.0, v3
	v_add_f32_e32 v7, 1.0, v6
	v_sub_f32_e32 v7, v3, v7
	v_add_f32_e32 v7, v5, v7
	v_add_f32_e32 v8, v6, v7
	v_sub_f32_e32 v6, v8, v6
	v_sub_f32_e32 v6, v7, v6
	v_add_f32_e32 v7, 1.0, v3
	v_add_f32_e32 v9, -1.0, v7
	v_sub_f32_e32 v3, v3, v9
	v_add_f32_e32 v3, v5, v3
	v_add_f32_e32 v5, v7, v3
	v_sub_f32_e32 v7, v5, v7
	v_sub_f32_e32 v3, v3, v7
	v_rcp_f32_e32 v7, v5
	v_cvt_f32_i32_e32 v4, v4
	s_mov_b32 s0, 0x3f317218
	v_mul_f32_e32 v9, v8, v7
	v_mul_f32_e32 v10, v5, v9
	v_fma_f32 v11, v9, v5, -v10
	v_fmac_f32_e32 v11, v9, v3
	v_add_f32_e32 v12, v10, v11
	v_sub_f32_e32 v13, v8, v12
	v_sub_f32_e32 v8, v8, v13
	v_sub_f32_e32 v10, v12, v10
	v_sub_f32_e32 v8, v8, v12
	v_add_f32_e32 v6, v6, v8
	v_sub_f32_e32 v8, v10, v11
	v_add_f32_e32 v6, v8, v6
	v_add_f32_e32 v8, v13, v6
	v_mul_f32_e32 v10, v7, v8
	v_mul_f32_e32 v11, v5, v10
	v_fma_f32 v5, v10, v5, -v11
	v_fmac_f32_e32 v5, v10, v3
	v_sub_f32_e32 v3, v13, v8
	v_add_f32_e32 v3, v6, v3
	v_add_f32_e32 v6, v11, v5
	v_sub_f32_e32 v12, v8, v6
	v_sub_f32_e32 v8, v8, v12
	v_sub_f32_e32 v11, v6, v11
	v_sub_f32_e32 v6, v8, v6
	v_add_f32_e32 v3, v3, v6
	v_sub_f32_e32 v5, v11, v5
	v_add_f32_e32 v3, v5, v3
	v_add_f32_e32 v5, v9, v10
	v_add_f32_e32 v3, v12, v3
	v_sub_f32_e32 v6, v5, v9
	v_mul_f32_e32 v3, v7, v3
	v_sub_f32_e32 v6, v10, v6
	v_add_f32_e32 v3, v6, v3
	v_mul_f32_e32 v9, 0x3f317218, v4
	v_add_f32_e32 v6, v5, v3
	v_fma_f32 v10, v4, s0, -v9
	v_mul_f32_e32 v7, v6, v6
	v_fmac_f32_e32 v10, 0xb102e308, v4
	v_sub_f32_e32 v4, v6, v5
	v_fmamk_f32 v8, v7, 0x3e9b6dac, v191
	v_sub_f32_e32 v3, v3, v4
	v_add_f32_e32 v4, v9, v10
	v_fmaak_f32 v8, v7, v8, 0x3f2aaada
	v_sub_f32_e32 v5, v4, v9
	v_ldexp_f32 v9, v6, 1
	v_mul_f32_e32 v6, v6, v7
	v_mul_f32_e32 v6, v6, v8
	v_add_f32_e32 v7, v9, v6
	v_sub_f32_e32 v8, v7, v9
	v_ldexp_f32 v3, v3, 1
	v_sub_f32_e32 v6, v6, v8
	v_add_f32_e32 v3, v3, v6
	v_add_f32_e32 v6, v7, v3
	v_sub_f32_e32 v7, v6, v7
	v_sub_f32_e32 v3, v3, v7
	v_add_f32_e32 v7, v4, v6
	v_sub_f32_e32 v8, v7, v4
	v_sub_f32_e32 v9, v7, v8
	v_sub_f32_e32 v5, v10, v5
	v_sub_f32_e32 v4, v4, v9
	v_sub_f32_e32 v6, v6, v8
	v_add_f32_e32 v4, v6, v4
	v_add_f32_e32 v6, v5, v3
	v_sub_f32_e32 v8, v6, v5
	v_sub_f32_e32 v9, v6, v8
	v_sub_f32_e32 v5, v5, v9
	v_sub_f32_e32 v3, v3, v8
	v_add_f32_e32 v4, v6, v4
	v_add_f32_e32 v3, v3, v5
	v_add_f32_e32 v5, v7, v4
	v_sub_f32_e32 v6, v5, v7
	v_sub_f32_e32 v4, v4, v6
	v_add_f32_e32 v3, v3, v4
	s_mov_b32 s0, 0x7f800000
	v_add_f32_e32 v3, v5, v3
	v_cmp_neq_f32_e64 s[0:1], s0, v1
	s_nop 1
	v_cndmask_b32_e64 v3, v199, v3, s[0:1]
	v_cmp_ngt_f32_e64 s[0:1], -1.0, v1
	s_nop 1
	v_cndmask_b32_e64 v3, v200, v3, s[0:1]
	v_cmp_neq_f32_e64 s[0:1], -1.0, v1
	s_nop 1
	v_cndmask_b32_e64 v3, v201, v3, s[0:1]
	s_mov_b32 s0, 0x33800000
	v_cmp_lt_f32_e64 s[38:39], |v1|, s0
	s_nop 1
	v_cndmask_b32_e64 v1, v3, v1, s[38:39]
	v_sub_f32_e32 v0, v0, v1
	v_add_u32_e32 v1, 0x11200, v2
	ds_write_b32 v1, v0

.LBB0_598:
	v_and_b32_e32 v10, 0x7e, v16
	v_ashrrev_i32_e32 v17, 3, v15
	v_mul_u32_u24_e32 v96, 0x3600, v10
	v_and_b32_e32 v12, -8, v17
	v_lshl_add_u64 v[0:1], s[6:7], 0, v[96:97]
	v_ashrrev_i32_e32 v13, 31, v12
	v_lshl_add_u64 v[0:1], v[12:13], 1, v[0:1]
	v_add_co_u32_e32 v4, vcc, 0x3000, v0
	v_readlane_b32 s8, v249, 19
	s_nop 0
	v_addc_co_u32_e32 v5, vcc, 0, v1, vcc
	global_load_dwordx4 v[0:3], v[0:1], off
	global_load_dwordx4 v[4:7], v[4:5], off offset:1536
	v_readlane_b32 s9, v249, 20
	s_andn2_b64 vcc, exec, s[8:9]
	s_waitcnt lgkmcnt(8)
	v_cndmask_b32_e64 v8, 0, 1, s[8:9]
	v_cmp_ne_u32_e64 s[38:39], 1, v8
	s_cbranch_vccnz .LBB0_600
	v_lshl_add_u32 v8, v10, 2, 0
	v_add_u32_e32 v8, 0x11600, v8
	ds_read_b64 v[8:9], v8
	s_branch .LBB0_601

.LBB0_717:
	s_or_b64 exec, exec, s[6:7]
	ds_write_b128 v70, v[52:55]
	ds_write_b128 v70, v[56:59] offset:4608
	ds_write_b128 v70, v[60:63] offset:9216
	ds_write_b128 v70, v[64:67] offset:13824
	s_waitcnt lgkmcnt(0)
	s_barrier
	ds_read_b128 v[32:35], v158
	ds_read_b128 v[36:39], v158 offset:4608
	s_waitcnt lgkmcnt(1)
	v_mfma_f32_32x32x16_bf16 v[80:95], v[98:101], v[32:35], 0
	s_waitcnt lgkmcnt(0)
	v_mfma_f32_32x32x16_bf16 v[48:63], v[98:101], v[36:39], 0
	ds_read_b128 v[32:35], v158 offset:9216
	ds_read_b128 v[36:39], v158 offset:13824
	s_waitcnt lgkmcnt(1)
	v_mfma_f32_32x32x16_bf16 v[64:79], v[98:101], v[32:35], 0
	s_waitcnt lgkmcnt(0)
	v_mfma_f32_32x32x16_bf16 v[32:47], v[98:101], v[36:39], 0
	ds_read_b128 v[148:151], v158 offset:32
	s_waitcnt lgkmcnt(0)
	v_mfma_f32_32x32x16_bf16 v[80:95], v[102:105], v[148:151], v[80:95]
	ds_read_b128 v[148:151], v158 offset:4640
	s_waitcnt lgkmcnt(0)
	v_mfma_f32_32x32x16_bf16 v[48:63], v[102:105], v[148:151], v[48:63]
	ds_read_b128 v[148:151], v158 offset:9248
	s_waitcnt lgkmcnt(0)
	v_mfma_f32_32x32x16_bf16 v[64:79], v[102:105], v[148:151], v[64:79]
	ds_read_b128 v[148:151], v158 offset:13856
	s_waitcnt lgkmcnt(0)
	v_mfma_f32_32x32x16_bf16 v[32:47], v[102:105], v[148:151], v[32:47]
	ds_read_b128 v[148:151], v158 offset:64
	s_waitcnt lgkmcnt(0)
	v_mfma_f32_32x32x16_bf16 v[80:95], v[106:109], v[148:151], v[80:95]
	ds_read_b128 v[148:151], v158 offset:4672
	s_waitcnt lgkmcnt(0)
	v_mfma_f32_32x32x16_bf16 v[48:63], v[106:109], v[148:151], v[48:63]
	ds_read_b128 v[148:151], v158 offset:9280
	s_waitcnt lgkmcnt(0)
	v_mfma_f32_32x32x16_bf16 v[64:79], v[106:109], v[148:151], v[64:79]
	ds_read_b128 v[148:151], v158 offset:13888
	s_waitcnt lgkmcnt(0)
	v_mfma_f32_32x32x16_bf16 v[32:47], v[106:109], v[148:151], v[32:47]
	ds_read_b128 v[148:151], v158 offset:96
	s_waitcnt lgkmcnt(0)
	v_mfma_f32_32x32x16_bf16 v[80:95], v[110:113], v[148:151], v[80:95]
	ds_read_b128 v[148:151], v158 offset:4704
	s_waitcnt lgkmcnt(0)
	v_mfma_f32_32x32x16_bf16 v[48:63], v[110:113], v[148:151], v[48:63]
	ds_read_b128 v[148:151], v158 offset:9312
	s_waitcnt lgkmcnt(0)
	v_mfma_f32_32x32x16_bf16 v[64:79], v[110:113], v[148:151], v[64:79]
	ds_read_b128 v[148:151], v158 offset:13920
	s_waitcnt lgkmcnt(0)
	v_mfma_f32_32x32x16_bf16 v[32:47], v[110:113], v[148:151], v[32:47]
	s_cmp_eq_u32 s53, 1
	s_cbranch_scc1 .Latt_nm
	s_cmp_gt_u32 s53, 2
	s_cbranch_scc1 .Latt_nm
	s_add_i32 s6, s53, s49
	v_mbcnt_hi_u32_b32 v148, -1, v195
	v_lshl_add_u32 v96, s6, 7, v183
	v_and_b32_e32 v147, 64, v148
	v_add_u32_e32 v149, 64, v147
	v_sub_u32_e32 v147, v96, v159
	v_cmp_gt_u32_e32 vcc, s58, v147
	s_or_b64 vcc, s[2:3], vcc
	v_add_u32_e32 v150, 32, v147
	v_cndmask_b32_e32 v80, v204, v80, vcc
	v_cmp_gt_u32_e32 vcc, s58, v150
	s_or_b64 vcc, s[2:3], vcc
	v_add_u32_e32 v151, 64, v147
	v_cndmask_b32_e32 v48, v204, v48, vcc
	v_cmp_gt_u32_e32 vcc, s58, v151
	s_or_b64 vcc, s[2:3], vcc
	v_add_u32_e32 v147, 0x60, v147
	v_cndmask_b32_e32 v64, v204, v64, vcc
	v_cmp_gt_u32_e32 vcc, s58, v147
	s_or_b64 vcc, s[2:3], vcc
	v_xor_b32_e32 v147, 16, v148
	v_cndmask_b32_e32 v32, v204, v32, vcc
	v_cmp_lt_i32_e32 vcc, v147, v149
	v_max3_f32 v150, v80, s59, v48
	v_max3_f32 v150, v150, v64, v32
	v_cndmask_b32_e32 v147, v148, v147, vcc
	v_lshlrev_b32_e32 v147, 2, v147
	v_mov_b32_e32 v151, v150
	v_mov_b32_e32 v255, v150
	s_nop 1
	v_permlane16_swap_b32_e32 v151, v255
	v_add_u32_e32 v187, 0x8800, v186
	v_add_u32_e32 v215, 0x9000, v186
	v_max_f32_e32 v150, v151, v255
	v_xor_b32_e32 v151, 8, v148
	v_cmp_lt_i32_e32 vcc, v151, v149
	s_nop 1
	v_cndmask_b32_e32 v151, v148, v151, vcc
	v_lshlrev_b32_e32 v208, 2, v151
	v_max_f32_dpp v150, v150, v150 row_ror:8 row_mask:0xf bank_mask:0xf
	v_xor_b32_e32 v151, 4, v148
	v_cmp_lt_i32_e32 vcc, v151, v149
	s_nop 1
	v_cndmask_b32_e32 v151, v148, v151, vcc
	v_lshlrev_b32_e32 v209, 2, v151
	v_mov_b32_dpp v151, v150 row_shl:4 row_mask:0xf bank_mask:0x5
	v_mov_b32_dpp v151, v150 row_shr:4 row_mask:0xf bank_mask:0xa
	v_max_f32_e32 v150, v150, v151
	v_xor_b32_e32 v151, 2, v148
	v_cmp_lt_i32_e32 vcc, v151, v149
	s_nop 1
	v_cndmask_b32_e32 v151, v148, v151, vcc
	v_lshlrev_b32_e32 v210, 2, v151
	v_max_f32_dpp v150, v150, v150 quad_perm:[2,3,0,1] row_mask:0xf bank_mask:0xf
	v_xor_b32_e32 v151, 1, v148
	v_cmp_lt_i32_e32 vcc, v151, v149
	v_sub_u32_e32 v149, v96, v161
	s_nop 0
	v_cndmask_b32_e32 v148, v148, v151, vcc
	v_cmp_gt_u32_e32 vcc, s58, v149
	s_or_b64 vcc, s[2:3], vcc
	v_lshlrev_b32_e32 v211, 2, v148
	v_cndmask_b32_e32 v151, v204, v81, vcc
	v_add_u32_e32 v81, 32, v149
	v_cmp_gt_u32_e32 vcc, s58, v81
	s_or_b64 vcc, s[2:3], vcc
	v_add_u32_e32 v81, 64, v149
	v_cndmask_b32_e32 v152, v204, v49, vcc
	v_cmp_gt_u32_e32 vcc, s58, v81
	s_or_b64 vcc, s[2:3], vcc
	v_max3_f32 v49, v151, s59, v152
	v_cndmask_b32_e32 v153, v204, v65, vcc
	v_add_u32_e32 v65, 0x60, v149
	v_cmp_gt_u32_e32 vcc, s58, v65
	s_or_b64 vcc, s[2:3], vcc
	v_mov_b32_dpp v148, v150 quad_perm:[1,0,3,2] row_mask:0xf bank_mask:0xf
	v_cndmask_b32_e32 v154, v204, v33, vcc
	v_max3_f32 v33, v49, v153, v154
	v_mov_b32_e32 v49, v33
	v_mov_b32_e32 v255, v33
	s_nop 1
	v_permlane16_swap_b32_e32 v49, v255
	v_max3_f32 v207, v130, v150, v148
	v_sub_f32_e32 v48, v48, v207
	v_mul_f32_e32 v48, 0x3fb8aa3b, v48
	v_max_f32_e32 v49, v49, v255
	v_sub_f32_e32 v33, v80, v207
	v_sub_f32_e32 v32, v32, v207
	v_mul_f32_e32 v32, 0x3fb8aa3b, v32
	v_sub_f32_e32 v130, v130, v207
	v_max_f32_dpp v65, v49, v49 row_ror:8 row_mask:0xf bank_mask:0xf
	s_nop 1
	v_mov_b32_dpp v80, v65 row_shl:4 row_mask:0xf bank_mask:0x5
	v_mov_b32_dpp v80, v65 row_shr:4 row_mask:0xf bank_mask:0xa
	v_exp_f32_e32 v49, v48
	v_sub_f32_e32 v48, v64, v207
	v_mul_f32_e32 v48, 0x3fb8aa3b, v48
	v_exp_f32_e32 v81, v48
	v_max_f32_e32 v64, v80, v80
	v_max_f32_e32 v64, v65, v64
	s_nop 1
	v_mov_b32_dpp v80, v64 quad_perm:[2,3,0,1] row_mask:0xf bank_mask:0xf
	v_exp_f32_e32 v65, v32
	v_mul_f32_e32 v33, 0x3fb8aa3b, v33
	v_exp_f32_e32 v33, v33
	v_max_f32_e32 v32, v80, v80
	v_max_f32_e32 v32, v64, v32
	s_nop 1
	v_mov_b32_dpp v48, v32 quad_perm:[1,0,3,2] row_mask:0xf bank_mask:0xf
	v_mul_f32_e32 v64, 0x3fb8aa3b, v130
	v_exp_f32_e32 v130, v64
	v_cvt_pk_bf16_f32 v148, v33, v49
	v_cvt_pk_bf16_f32 v149, v81, v65
	v_max3_f32 v206, v131, v32, v48
	v_sub_u32_e32 v32, v96, v169
	v_cmp_gt_u32_e32 vcc, s58, v32
	s_or_b64 vcc, s[2:3], vcc
	v_add_u32_e32 v48, 32, v32
	v_cndmask_b32_e32 v82, v204, v82, vcc
	v_cmp_gt_u32_e32 vcc, s58, v48
	s_or_b64 vcc, s[2:3], vcc
	v_add_u32_e32 v64, 64, v32
	v_cndmask_b32_e32 v50, v204, v50, vcc
	v_cmp_gt_u32_e32 vcc, s58, v64
	s_or_b64 vcc, s[2:3], vcc
	v_add_u32_e32 v32, 0x60, v32
	v_cndmask_b32_e32 v66, v204, v66, vcc
	v_cmp_gt_u32_e32 vcc, s58, v32
	s_or_b64 vcc, s[2:3], vcc
	v_max3_f32 v48, v82, s59, v50
	v_cndmask_b32_e32 v34, v204, v34, vcc
	v_max3_f32 v48, v48, v66, v34
	v_mov_b32_e32 v64, v48
	v_mov_b32_e32 v255, v48
	s_nop 1
	v_permlane16_swap_b32_e32 v64, v255
	v_sub_f32_e32 v32, v151, v206
	v_sub_f32_e32 v80, v152, v206
	v_mul_f32_e32 v32, 0x3fb8aa3b, v32
	v_exp_f32_e32 v32, v32
	v_max_f32_e32 v64, v64, v255
	v_mul_f32_e32 v48, 0x3fb8aa3b, v80
	v_sub_f32_e32 v80, v153, v206
	v_mul_f32_e32 v80, 0x3fb8aa3b, v80
	v_exp_f32_e32 v48, v48
	v_max_f32_dpp v150, v64, v64 row_ror:8 row_mask:0xf bank_mask:0xf
	v_sub_f32_e32 v64, v154, v206
	v_sub_u32_e32 v154, v96, v170
	v_cmp_gt_u32_e32 vcc, s58, v154
	s_or_b64 vcc, s[2:3], vcc
	v_mov_b32_dpp v151, v150 row_shl:4 row_mask:0xf bank_mask:0x5
	v_mov_b32_dpp v151, v150 row_shr:4 row_mask:0xf bank_mask:0xa
	v_cndmask_b32_e32 v155, v204, v83, vcc
	v_add_u32_e32 v83, 32, v154
	v_cmp_gt_u32_e32 vcc, s58, v83
	s_or_b64 vcc, s[2:3], vcc
	v_add_u32_e32 v83, 64, v154
	v_cndmask_b32_e32 v156, v204, v51, vcc
	v_cmp_gt_u32_e32 vcc, s58, v83
	s_or_b64 vcc, s[2:3], vcc
	v_max3_f32 v51, v155, s59, v156
	v_cndmask_b32_e32 v160, v204, v67, vcc
	v_add_u32_e32 v67, 0x60, v154
	v_cmp_gt_u32_e32 vcc, s58, v67
	s_or_b64 vcc, s[2:3], vcc
	v_max_f32_e32 v151, v151, v151
	v_cndmask_b32_e32 v154, v204, v35, vcc
	v_max3_f32 v35, v51, v160, v154
	v_max_f32_e32 v152, v150, v151
	v_mov_b32_e32 v51, v35
	v_mov_b32_e32 v255, v35
	s_nop 1
	v_permlane16_swap_b32_e32 v51, v255
	v_mov_b32_dpp v153, v152 quad_perm:[2,3,0,1] row_mask:0xf bank_mask:0xf
	v_mul_f32_e32 v64, 0x3fb8aa3b, v64
	v_exp_f32_e32 v80, v80
	v_exp_f32_e32 v64, v64
	v_max_f32_e32 v153, v153, v153
	v_max_f32_e32 v51, v51, v255
	v_max_f32_e32 v152, v152, v153
	s_nop 1
	v_mov_b32_dpp v153, v152 quad_perm:[1,0,3,2] row_mask:0xf bank_mask:0xf
	v_cvt_pk_bf16_f32 v150, v32, v48
	v_cvt_pk_bf16_f32 v151, v80, v64
	ds_write2_b64 v187, v[148:149], v[150:151] offset0:128 offset1:162
	v_max3_f32 v189, v132, v152, v153
	v_max_f32_dpp v67, v51, v51 row_ror:8 row_mask:0xf bank_mask:0xf
	v_sub_f32_e32 v35, v82, v189
	s_nop 1
	v_mov_b32_dpp v82, v67 row_shl:4 row_mask:0xf bank_mask:0x5
	v_mov_b32_dpp v82, v67 row_shr:4 row_mask:0xf bank_mask:0xa
	v_sub_f32_e32 v50, v50, v189
	v_mul_f32_e32 v50, 0x3fb8aa3b, v50
	v_exp_f32_e32 v51, v50
	v_sub_f32_e32 v50, v66, v189
	s_waitcnt lgkmcnt(0)
	v_max_f32_e32 v66, v82, v82
	v_max_f32_e32 v66, v67, v66
	s_nop 1
	v_mov_b32_dpp v82, v66 quad_perm:[2,3,0,1] row_mask:0xf bank_mask:0xf
	v_sub_f32_e32 v34, v34, v189
	v_mul_f32_e32 v34, 0x3fb8aa3b, v34
	v_exp_f32_e32 v67, v34
	v_mul_f32_e32 v50, 0x3fb8aa3b, v50
	v_max_f32_e32 v34, v82, v82
	v_max_f32_e32 v34, v66, v34
	v_exp_f32_e32 v83, v50
	s_nop 1
	v_mov_b32_dpp v50, v34 quad_perm:[1,0,3,2] row_mask:0xf bank_mask:0xf
	v_sub_f32_e32 v132, v132, v189
	v_mul_f32_e32 v66, 0x3fb8aa3b, v132
	v_exp_f32_e32 v132, v66
	v_mul_f32_e32 v35, 0x3fb8aa3b, v35
	v_max3_f32 v188, v133, v34, v50
	v_sub_u32_e32 v34, v96, v171
	v_cmp_gt_u32_e32 vcc, s58, v34
	s_or_b64 vcc, s[2:3], vcc
	v_add_u32_e32 v50, 32, v34
	v_cndmask_b32_e32 v84, v204, v84, vcc
	v_cmp_gt_u32_e32 vcc, s58, v50
	s_or_b64 vcc, s[2:3], vcc
	v_add_u32_e32 v66, 64, v34
	v_cndmask_b32_e32 v52, v204, v52, vcc
	v_cmp_gt_u32_e32 vcc, s58, v66
	s_or_b64 vcc, s[2:3], vcc
	v_add_u32_e32 v34, 0x60, v34
	v_cndmask_b32_e32 v68, v204, v68, vcc
	v_cmp_gt_u32_e32 vcc, s58, v34
	s_or_b64 vcc, s[2:3], vcc
	v_max3_f32 v50, v84, s59, v52
	v_cndmask_b32_e32 v150, v204, v36, vcc
	v_max3_f32 v34, v50, v68, v150
	v_mov_b32_e32 v36, v34
	v_mov_b32_e32 v255, v34
	s_nop 1
	v_permlane16_swap_b32_e32 v36, v255
	v_sub_f32_e32 v151, v154, v188
	v_sub_f32_e32 v50, v133, v188
	v_mul_f32_e32 v133, 0x3fb8aa3b, v50
	v_sub_f32_e32 v50, v155, v188
	v_max_f32_e32 v36, v36, v255
	s_nop 1
	v_mov_b32_dpp v66, v36 row_ror:8 row_mask:0xf bank_mask:0xf
	v_mul_f32_e32 v50, 0x3fb8aa3b, v50
	v_exp_f32_e32 v34, v50
	v_sub_f32_e32 v50, v156, v188
	v_sub_f32_e32 v82, v160, v188
	v_max_f32_e32 v66, v66, v66
	v_max_f32_e32 v36, v36, v66
	s_nop 1
	v_mov_b32_dpp v66, v36 row_shl:4 row_mask:0xf bank_mask:0x5
	v_mov_b32_dpp v66, v36 row_shr:4 row_mask:0xf bank_mask:0xa
	v_mul_f32_e32 v50, 0x3fb8aa3b, v50
	v_mul_f32_e32 v82, 0x3fb8aa3b, v82
	v_exp_f32_e32 v35, v35
	v_exp_f32_e32 v50, v50
	v_max_f32_e32 v66, v66, v66
	v_max_f32_e32 v152, v36, v66
	s_nop 1
	v_mov_b32_dpp v153, v152 quad_perm:[2,3,0,1] row_mask:0xf bank_mask:0xf
	v_mul_f32_e32 v36, 0x3fb8aa3b, v151
	v_exp_f32_e32 v82, v82
	v_exp_f32_e32 v66, v36
	v_cvt_pk_bf16_f32 v148, v35, v51
	v_max_f32_e32 v151, v153, v153
	v_sub_u32_e32 v153, v96, v172
	v_cmp_gt_u32_e32 vcc, s58, v153
	s_or_b64 vcc, s[2:3], vcc
	v_cvt_pk_bf16_f32 v149, v83, v67
	v_cndmask_b32_e32 v154, v204, v85, vcc
	v_add_u32_e32 v85, 32, v153
	v_cmp_gt_u32_e32 vcc, s58, v85
	s_or_b64 vcc, s[2:3], vcc
	v_add_u32_e32 v85, 64, v153
	v_cndmask_b32_e32 v155, v204, v53, vcc
	v_cmp_gt_u32_e32 vcc, s58, v85
	s_or_b64 vcc, s[2:3], vcc
	v_max3_f32 v53, v154, s59, v155
	v_cndmask_b32_e32 v156, v204, v69, vcc
	v_add_u32_e32 v69, 0x60, v153
	v_cmp_gt_u32_e32 vcc, s58, v69
	s_or_b64 vcc, s[2:3], vcc
	v_cvt_pk_bf16_f32 v36, v34, v50
	v_cndmask_b32_e32 v153, v204, v37, vcc
	v_max3_f32 v53, v53, v156, v153
	v_mov_b32_e32 v69, v53
	v_mov_b32_e32 v255, v53
	s_nop 1
	v_permlane16_swap_b32_e32 v69, v255
	s_nop 1
	v_mov_b32_dpp v69, v255 quad_perm:[0,1,2,3] row_mask:0x5 bank_mask:0xf
	v_cvt_pk_bf16_f32 v37, v82, v66
	ds_write2_b64 v187, v[148:149], v[36:37] offset0:196 offset1:230
	v_max_f32_e32 v151, v152, v151
	s_nop 1
	v_mov_b32_dpp v152, v151 quad_perm:[1,0,3,2] row_mask:0xf bank_mask:0xf
	v_max_f32_e32 v37, v69, v69
	v_max_f32_e32 v53, v53, v37
	v_sub_f32_e32 v131, v131, v206
	s_waitcnt lgkmcnt(0)
	v_max3_f32 v187, v134, v151, v152
	v_sub_f32_e32 v37, v84, v187
	v_sub_f32_e32 v52, v52, v187
	v_max_f32_dpp v69, v53, v53 row_ror:8 row_mask:0xf bank_mask:0xf
	s_nop 1
	v_mov_b32_dpp v84, v69 row_shl:4 row_mask:0xf bank_mask:0x5
	v_mov_b32_dpp v84, v69 row_shr:4 row_mask:0xf bank_mask:0xa
	v_mul_f32_e32 v52, 0x3fb8aa3b, v52
	v_exp_f32_e32 v53, v52
	v_sub_f32_e32 v52, v68, v187
	v_mul_f32_e32 v52, 0x3fb8aa3b, v52
	v_max_f32_e32 v68, v84, v84
	v_max_f32_e32 v68, v69, v68
	s_nop 1
	v_mov_b32_dpp v84, v68 quad_perm:[2,3,0,1] row_mask:0xf bank_mask:0xf
	v_exp_f32_e32 v85, v52
	v_sub_f32_e32 v52, v150, v187
	v_mul_f32_e32 v52, 0x3fb8aa3b, v52
	v_exp_f32_e32 v69, v52
	v_max_f32_e32 v52, v84, v84
	v_max_f32_e32 v52, v68, v52
	s_nop 1
	v_mov_b32_dpp v68, v52 quad_perm:[1,0,3,2] row_mask:0xf bank_mask:0xf
	v_sub_f32_e32 v36, v134, v187
	v_mul_f32_e32 v36, 0x3fb8aa3b, v36
	v_exp_f32_e32 v134, v36
	v_sub_u32_e32 v36, v96, v173
	v_cmp_gt_u32_e32 vcc, s58, v36
	v_max3_f32 v160, v135, v52, v68
	s_or_b64 vcc, s[2:3], vcc
	v_add_u32_e32 v52, 32, v36
	v_cndmask_b32_e32 v86, v204, v86, vcc
	v_cmp_gt_u32_e32 vcc, s58, v52
	s_or_b64 vcc, s[2:3], vcc
	v_add_u32_e32 v68, 64, v36
	v_cndmask_b32_e32 v54, v204, v54, vcc
	v_cmp_gt_u32_e32 vcc, s58, v68
	s_or_b64 vcc, s[2:3], vcc
	v_add_u32_e32 v36, 0x60, v36
	v_cndmask_b32_e32 v70, v204, v70, vcc
	v_cmp_gt_u32_e32 vcc, s58, v36
	s_or_b64 vcc, s[2:3], vcc
	v_max3_f32 v52, v86, s59, v54
	v_cndmask_b32_e32 v38, v204, v38, vcc
	v_max3_f32 v52, v52, v70, v38
	v_mov_b32_e32 v68, v52
	v_mov_b32_e32 v255, v52
	s_nop 1
	v_permlane16_swap_b32_e32 v68, v255
	v_sub_f32_e32 v36, v154, v160
	v_sub_u32_e32 v154, v96, v174
	v_cmp_gt_u32_e32 vcc, s58, v154
	s_or_b64 vcc, s[2:3], vcc
	v_max_f32_e32 v68, v68, v255
	v_cndmask_b32_e32 v212, v204, v87, vcc
	v_add_u32_e32 v87, 32, v154
	v_cmp_gt_u32_e32 vcc, s58, v87
	s_or_b64 vcc, s[2:3], vcc
	v_add_u32_e32 v87, 64, v154
	v_max_f32_dpp v150, v68, v68 row_ror:8 row_mask:0xf bank_mask:0xf
	v_cndmask_b32_e32 v213, v204, v55, vcc
	v_cmp_gt_u32_e32 vcc, s58, v87
	v_mov_b32_dpp v151, v150 row_shl:4 row_mask:0xf bank_mask:0x5
	v_mov_b32_dpp v151, v150 row_shr:4 row_mask:0xf bank_mask:0xa
	s_or_b64 vcc, s[2:3], vcc
	v_cndmask_b32_e32 v214, v204, v71, vcc
	v_add_u32_e32 v71, 0x60, v154
	v_cmp_gt_u32_e32 vcc, s58, v71
	s_or_b64 vcc, s[2:3], vcc
	v_max3_f32 v55, v212, s59, v213
	v_cndmask_b32_e32 v154, v204, v39, vcc
	v_max_f32_e32 v151, v151, v151
	v_max3_f32 v39, v55, v214, v154
	v_max_f32_e32 v152, v150, v151
	v_mov_b32_e32 v55, v39
	v_mov_b32_e32 v255, v39
	s_nop 1
	v_permlane16_swap_b32_e32 v55, v255
	v_sub_f32_e32 v68, v153, v160
	v_mov_b32_dpp v153, v152 quad_perm:[2,3,0,1] row_mask:0xf bank_mask:0xf
	v_sub_f32_e32 v84, v155, v160
	v_mul_f32_e32 v52, 0x3fb8aa3b, v84
	v_max_f32_e32 v55, v55, v255
	v_max_f32_e32 v153, v153, v153
	v_max_f32_e32 v152, v152, v153
	s_nop 0
	s_nop 1
	v_mov_b32_dpp v153, v152 quad_perm:[1,0,3,2] row_mask:0xf bank_mask:0xf
	v_sub_f32_e32 v84, v156, v160
	v_mul_f32_e32 v37, 0x3fb8aa3b, v37
	v_mul_f32_e32 v36, 0x3fb8aa3b, v36
	v_max3_f32 v156, v136, v152, v153
	v_max_f32_dpp v71, v55, v55 row_ror:8 row_mask:0xf bank_mask:0xf
	v_sub_f32_e32 v39, v86, v156
	s_nop 1
	v_mov_b32_dpp v86, v71 row_shl:4 row_mask:0xf bank_mask:0x5
	v_mov_b32_dpp v86, v71 row_shr:4 row_mask:0xf bank_mask:0xa
	v_sub_f32_e32 v54, v54, v156
	v_mul_f32_e32 v54, 0x3fb8aa3b, v54
	v_exp_f32_e32 v55, v54
	v_sub_f32_e32 v54, v70, v156
	v_max_f32_e32 v70, v86, v86
	v_max_f32_e32 v70, v71, v70
	s_nop 1
	v_mov_b32_dpp v86, v70 quad_perm:[2,3,0,1] row_mask:0xf bank_mask:0xf
	v_sub_f32_e32 v38, v38, v156
	v_mul_f32_e32 v38, 0x3fb8aa3b, v38
	v_exp_f32_e32 v71, v38
	v_mul_f32_e32 v54, 0x3fb8aa3b, v54
	v_max_f32_e32 v38, v86, v86
	v_max_f32_e32 v38, v70, v38
	v_exp_f32_e32 v87, v54
	s_nop 1
	v_mov_b32_dpp v54, v38 quad_perm:[1,0,3,2] row_mask:0xf bank_mask:0xf
	v_sub_f32_e32 v136, v136, v156
	v_mul_f32_e32 v84, 0x3fb8aa3b, v84
	v_mul_f32_e32 v68, 0x3fb8aa3b, v68
	v_mul_f32_e32 v70, 0x3fb8aa3b, v136
	v_max3_f32 v155, v137, v38, v54
	v_sub_u32_e32 v38, v96, v175
	v_cmp_gt_u32_e32 vcc, s58, v38
	s_or_b64 vcc, s[2:3], vcc
	v_add_u32_e32 v54, 32, v38
	v_cndmask_b32_e32 v88, v204, v88, vcc
	v_cmp_gt_u32_e32 vcc, s58, v54
	v_exp_f32_e32 v37, v37
	v_exp_f32_e32 v36, v36
	v_exp_f32_e32 v52, v52
	v_exp_f32_e32 v84, v84
	v_exp_f32_e32 v68, v68
	v_exp_f32_e32 v136, v70
	s_or_b64 vcc, s[2:3], vcc
	v_add_u32_e32 v70, 64, v38
	v_cndmask_b32_e32 v56, v204, v56, vcc
	v_cmp_gt_u32_e32 vcc, s58, v70
	s_or_b64 vcc, s[2:3], vcc
	v_add_u32_e32 v38, 0x60, v38
	v_cndmask_b32_e32 v72, v204, v72, vcc
	v_cmp_gt_u32_e32 vcc, s58, v38
	v_cvt_pk_bf16_f32 v148, v37, v53
	v_cvt_pk_bf16_f32 v149, v85, v69
	v_cvt_pk_bf16_f32 v150, v36, v52
	v_cvt_pk_bf16_f32 v151, v84, v68
	s_or_b64 vcc, s[2:3], vcc
	ds_write2_b64 v215, v[148:149], v[150:151] offset0:144 offset1:178
	v_max3_f32 v54, v88, s59, v56
	v_cndmask_b32_e32 v150, v204, v40, vcc
	v_max3_f32 v38, v54, v72, v150
	v_mov_b32_e32 v40, v38
	v_mov_b32_e32 v255, v38
	s_nop 1
	v_permlane16_swap_b32_e32 v40, v255
	v_sub_f32_e32 v151, v154, v155
	v_sub_f32_e32 v54, v137, v155
	v_mul_f32_e32 v137, 0x3fb8aa3b, v54
	v_sub_f32_e32 v54, v212, v155
	s_waitcnt lgkmcnt(0)
	v_max_f32_e32 v40, v40, v255
	s_nop 1
	v_mov_b32_dpp v70, v40 row_ror:8 row_mask:0xf bank_mask:0xf
	v_mul_f32_e32 v54, 0x3fb8aa3b, v54
	v_exp_f32_e32 v38, v54
	v_sub_f32_e32 v54, v213, v155
	v_sub_f32_e32 v86, v214, v155
	v_max_f32_e32 v70, v70, v70
	v_max_f32_e32 v40, v40, v70
	s_nop 1
	v_mov_b32_dpp v70, v40 row_shl:4 row_mask:0xf bank_mask:0x5
	v_mov_b32_dpp v70, v40 row_shr:4 row_mask:0xf bank_mask:0xa
	v_mul_f32_e32 v39, 0x3fb8aa3b, v39
	v_mul_f32_e32 v54, 0x3fb8aa3b, v54
	v_mul_f32_e32 v86, 0x3fb8aa3b, v86
	v_exp_f32_e32 v39, v39
	v_max_f32_e32 v70, v70, v70
	v_max_f32_e32 v152, v40, v70
	s_nop 1
	v_mov_b32_dpp v153, v152 quad_perm:[2,3,0,1] row_mask:0xf bank_mask:0xf
	v_mul_f32_e32 v40, 0x3fb8aa3b, v151
	v_exp_f32_e32 v54, v54
	v_exp_f32_e32 v86, v86
	v_exp_f32_e32 v70, v40
	v_max_f32_e32 v151, v153, v153
	v_sub_u32_e32 v153, v96, v176
	v_cmp_gt_u32_e32 vcc, s58, v153
	s_or_b64 vcc, s[2:3], vcc
	v_cvt_pk_bf16_f32 v148, v39, v55
	v_cndmask_b32_e32 v212, v204, v89, vcc
	v_add_u32_e32 v89, 32, v153
	v_cmp_gt_u32_e32 vcc, s58, v89
	s_or_b64 vcc, s[2:3], vcc
	v_add_u32_e32 v89, 64, v153
	v_cndmask_b32_e32 v213, v204, v57, vcc
	v_cmp_gt_u32_e32 vcc, s58, v89
	s_or_b64 vcc, s[2:3], vcc
	v_max3_f32 v57, v212, s59, v213
	v_cndmask_b32_e32 v214, v204, v73, vcc
	v_add_u32_e32 v73, 0x60, v153
	v_cmp_gt_u32_e32 vcc, s58, v73
	s_or_b64 vcc, s[2:3], vcc
	v_cvt_pk_bf16_f32 v149, v87, v71
	v_cndmask_b32_e32 v216, v204, v41, vcc
	v_max3_f32 v57, v57, v214, v216
	v_mov_b32_e32 v73, v57
	v_mov_b32_e32 v255, v57
	s_nop 1
	v_permlane16_swap_b32_e32 v73, v255
	s_nop 1
	v_mov_b32_dpp v73, v255 quad_perm:[0,1,2,3] row_mask:0x5 bank_mask:0xf
	v_cvt_pk_bf16_f32 v40, v38, v54
	v_cvt_pk_bf16_f32 v41, v86, v70
	ds_write2_b64 v215, v[148:149], v[40:41] offset0:212 offset1:246
	v_max_f32_e32 v151, v152, v151
	v_max_f32_e32 v41, v73, v73
	v_max_f32_e32 v57, v57, v41
	v_mov_b32_dpp v152, v151 quad_perm:[1,0,3,2] row_mask:0xf bank_mask:0xf
	v_sub_f32_e32 v135, v135, v160
	v_mul_f32_e32 v131, 0x3fb8aa3b, v131
	v_mul_f32_e32 v135, 0x3fb8aa3b, v135
	s_waitcnt lgkmcnt(0)
	v_max3_f32 v154, v138, v151, v152
	v_max_f32_dpp v73, v57, v57 row_ror:8 row_mask:0xf bank_mask:0xf
	v_sub_f32_e32 v41, v88, v154
	s_nop 1
	v_mov_b32_dpp v88, v73 row_shl:4 row_mask:0xf bank_mask:0x5
	v_mov_b32_dpp v88, v73 row_shr:4 row_mask:0xf bank_mask:0xa
	v_sub_f32_e32 v56, v56, v154
	v_mul_f32_e32 v56, 0x3fb8aa3b, v56
	v_exp_f32_e32 v57, v56
	v_sub_f32_e32 v56, v72, v154
	v_max_f32_e32 v72, v88, v88
	v_max_f32_e32 v72, v73, v72
	s_nop 1
	v_mov_b32_dpp v88, v72 quad_perm:[2,3,0,1] row_mask:0xf bank_mask:0xf
	v_mul_f32_e32 v56, 0x3fb8aa3b, v56
	v_exp_f32_e32 v89, v56
	v_sub_f32_e32 v56, v150, v154
	v_mul_f32_e32 v56, 0x3fb8aa3b, v56
	v_exp_f32_e32 v73, v56
	v_max_f32_e32 v56, v88, v88
	v_max_f32_e32 v56, v72, v56
	s_nop 1
	v_mov_b32_dpp v72, v56 quad_perm:[1,0,3,2] row_mask:0xf bank_mask:0xf
	v_sub_f32_e32 v40, v138, v154
	v_mul_f32_e32 v40, 0x3fb8aa3b, v40
	v_exp_f32_e32 v138, v40
	v_sub_u32_e32 v40, v96, v177
	v_cmp_gt_u32_e32 vcc, s58, v40
	v_max3_f32 v153, v139, v56, v72
	s_or_b64 vcc, s[2:3], vcc
	v_add_u32_e32 v56, 32, v40
	v_cndmask_b32_e32 v90, v204, v90, vcc
	v_cmp_gt_u32_e32 vcc, s58, v56
	s_or_b64 vcc, s[2:3], vcc
	v_add_u32_e32 v72, 64, v40
	v_cndmask_b32_e32 v58, v204, v58, vcc
	v_cmp_gt_u32_e32 vcc, s58, v72
	s_or_b64 vcc, s[2:3], vcc
	v_add_u32_e32 v40, 0x60, v40
	v_cndmask_b32_e32 v74, v204, v74, vcc
	v_cmp_gt_u32_e32 vcc, s58, v40
	s_or_b64 vcc, s[2:3], vcc
	v_max3_f32 v56, v90, s59, v58
	v_cndmask_b32_e32 v42, v204, v42, vcc
	v_max3_f32 v56, v56, v74, v42
	v_mov_b32_e32 v72, v56
	v_mov_b32_e32 v255, v56
	s_nop 1
	v_permlane16_swap_b32_e32 v72, v255
	v_sub_f32_e32 v88, v213, v153
	v_sub_u32_e32 v213, v96, v178
	v_cmp_gt_u32_e32 vcc, s58, v213
	s_or_b64 vcc, s[2:3], vcc
	v_max_f32_e32 v72, v72, v255
	v_mul_f32_e32 v56, 0x3fb8aa3b, v88
	v_sub_f32_e32 v88, v214, v153
	v_cndmask_b32_e32 v214, v204, v91, vcc
	v_add_u32_e32 v91, 32, v213
	v_cmp_gt_u32_e32 vcc, s58, v91
	s_or_b64 vcc, s[2:3], vcc
	v_add_u32_e32 v91, 64, v213
	v_max_f32_dpp v150, v72, v72 row_ror:8 row_mask:0xf bank_mask:0xf
	v_cndmask_b32_e32 v215, v204, v59, vcc
	v_cmp_gt_u32_e32 vcc, s58, v91
	v_mov_b32_dpp v151, v150 row_shl:4 row_mask:0xf bank_mask:0x5
	v_mov_b32_dpp v151, v150 row_shr:4 row_mask:0xf bank_mask:0xa
	s_or_b64 vcc, s[2:3], vcc
	v_sub_f32_e32 v72, v216, v153
	v_cndmask_b32_e32 v216, v204, v75, vcc
	v_add_u32_e32 v75, 0x60, v213
	v_cmp_gt_u32_e32 vcc, s58, v75
	s_or_b64 vcc, s[2:3], vcc
	v_max3_f32 v59, v214, s59, v215
	v_cndmask_b32_e32 v213, v204, v43, vcc
	v_max_f32_e32 v151, v151, v151
	v_max3_f32 v43, v59, v216, v213
	v_sub_f32_e32 v40, v212, v153
	v_max_f32_e32 v152, v150, v151
	v_mov_b32_e32 v59, v43
	v_mov_b32_e32 v255, v43
	s_nop 1
	v_permlane16_swap_b32_e32 v59, v255
	v_mul_f32_e32 v41, 0x3fb8aa3b, v41
	v_mul_f32_e32 v40, 0x3fb8aa3b, v40
	v_mul_f32_e32 v88, 0x3fb8aa3b, v88
	v_mul_f32_e32 v72, 0x3fb8aa3b, v72
	v_mov_b32_dpp v212, v152 quad_perm:[2,3,0,1] row_mask:0xf bank_mask:0xf
	v_exp_f32_e32 v41, v41
	v_exp_f32_e32 v40, v40
	v_exp_f32_e32 v56, v56
	v_exp_f32_e32 v88, v88
	v_exp_f32_e32 v72, v72
	v_cvt_pk_bf16_f32 v148, v41, v57
	v_cvt_pk_bf16_f32 v149, v89, v73
	v_cvt_pk_bf16_f32 v150, v40, v56
	v_cvt_pk_bf16_f32 v151, v88, v72
	v_max_f32_e32 v212, v212, v212
	v_add_u32_e32 v75, 0x9800, v186
	v_max_f32_e32 v59, v59, v255
	v_max_f32_e32 v152, v152, v212
	ds_write2_b64 v75, v[148:149], v[150:151] offset0:160 offset1:194
	s_nop 0
	v_mov_b32_dpp v212, v152 quad_perm:[1,0,3,2] row_mask:0xf bank_mask:0xf
	v_sub_f32_e32 v139, v139, v153
	v_mul_f32_e32 v139, 0x3fb8aa3b, v139
	v_exp_f32_e32 v131, v131
	s_waitcnt lgkmcnt(0)
	v_max3_f32 v152, v140, v152, v212
	v_max_f32_dpp v75, v59, v59 row_ror:8 row_mask:0xf bank_mask:0xf
	v_sub_f32_e32 v43, v90, v152
	s_nop 1
	v_mov_b32_dpp v90, v75 row_shl:4 row_mask:0xf bank_mask:0x5
	v_mov_b32_dpp v90, v75 row_shr:4 row_mask:0xf bank_mask:0xa
	v_sub_f32_e32 v58, v58, v152
	v_mul_f32_e32 v58, 0x3fb8aa3b, v58
	v_exp_f32_e32 v59, v58
	v_sub_f32_e32 v58, v74, v152
	v_max_f32_e32 v74, v90, v90
	v_max_f32_e32 v74, v75, v74
	s_nop 1
	v_mov_b32_dpp v90, v74 quad_perm:[2,3,0,1] row_mask:0xf bank_mask:0xf
	v_sub_f32_e32 v42, v42, v152
	v_mul_f32_e32 v42, 0x3fb8aa3b, v42
	v_exp_f32_e32 v75, v42
	v_mul_f32_e32 v58, 0x3fb8aa3b, v58
	v_max_f32_e32 v42, v90, v90
	v_max_f32_e32 v42, v74, v42
	v_exp_f32_e32 v91, v58
	s_nop 1
	v_mov_b32_dpp v58, v42 quad_perm:[1,0,3,2] row_mask:0xf bank_mask:0xf
	v_sub_f32_e32 v140, v140, v152
	v_mul_f32_e32 v74, 0x3fb8aa3b, v140
	v_exp_f32_e32 v140, v74
	v_mul_f32_e32 v43, 0x3fb8aa3b, v43
	v_max3_f32 v151, v141, v42, v58
	v_sub_u32_e32 v42, v96, v179
	v_cmp_gt_u32_e32 vcc, s58, v42
	s_or_b64 vcc, s[2:3], vcc
	v_add_u32_e32 v58, 32, v42
	v_cndmask_b32_e32 v92, v204, v92, vcc
	v_cmp_gt_u32_e32 vcc, s58, v58
	s_or_b64 vcc, s[2:3], vcc
	v_add_u32_e32 v74, 64, v42
	v_cndmask_b32_e32 v60, v204, v60, vcc
	v_cmp_gt_u32_e32 vcc, s58, v74
	s_or_b64 vcc, s[2:3], vcc
	v_add_u32_e32 v42, 0x60, v42
	v_cndmask_b32_e32 v76, v204, v76, vcc
	v_cmp_gt_u32_e32 vcc, s58, v42
	s_or_b64 vcc, s[2:3], vcc
	v_max3_f32 v58, v92, s59, v60
	v_cndmask_b32_e32 v44, v204, v44, vcc
	v_max3_f32 v58, v58, v76, v44
	v_mov_b32_e32 v74, v58
	v_mov_b32_e32 v255, v58
	s_nop 1
	v_permlane16_swap_b32_e32 v74, v255
	v_sub_f32_e32 v90, v215, v151
	v_sub_u32_e32 v215, v96, v180
	v_cmp_gt_u32_e32 vcc, s58, v215
	s_or_b64 vcc, s[2:3], vcc
	v_max_f32_e32 v74, v74, v255
	v_mul_f32_e32 v58, 0x3fb8aa3b, v90
	v_sub_f32_e32 v90, v216, v151
	v_cndmask_b32_e32 v216, v204, v93, vcc
	v_add_u32_e32 v93, 32, v215
	v_cmp_gt_u32_e32 vcc, s58, v93
	s_or_b64 vcc, s[2:3], vcc
	v_add_u32_e32 v93, 64, v215
	v_max_f32_dpp v150, v74, v74 row_ror:8 row_mask:0xf bank_mask:0xf
	v_cndmask_b32_e32 v217, v204, v61, vcc
	v_cmp_gt_u32_e32 vcc, s58, v93
	v_mov_b32_dpp v212, v150 row_shl:4 row_mask:0xf bank_mask:0x5
	v_mov_b32_dpp v212, v150 row_shr:4 row_mask:0xf bank_mask:0xa
	s_or_b64 vcc, s[2:3], vcc
	v_cndmask_b32_e32 v218, v204, v77, vcc
	v_add_u32_e32 v77, 0x60, v215
	v_cmp_gt_u32_e32 vcc, s58, v77
	s_or_b64 vcc, s[2:3], vcc
	v_max3_f32 v61, v216, s59, v217
	v_cndmask_b32_e32 v215, v204, v45, vcc
	v_max_f32_e32 v212, v212, v212
	v_max3_f32 v45, v61, v218, v215
	v_sub_f32_e32 v42, v214, v151
	v_sub_f32_e32 v74, v213, v151
	v_max_f32_e32 v150, v150, v212
	v_mov_b32_e32 v61, v45
	v_mov_b32_e32 v255, v45
	s_nop 1
	v_permlane16_swap_b32_e32 v61, v255
	v_mul_f32_e32 v42, 0x3fb8aa3b, v42
	v_mul_f32_e32 v90, 0x3fb8aa3b, v90
	v_mul_f32_e32 v74, 0x3fb8aa3b, v74
	v_mov_b32_dpp v214, v150 quad_perm:[2,3,0,1] row_mask:0xf bank_mask:0xf
	v_exp_f32_e32 v43, v43
	v_exp_f32_e32 v42, v42
	v_exp_f32_e32 v58, v58
	v_exp_f32_e32 v90, v90
	v_exp_f32_e32 v74, v74
	v_cvt_pk_bf16_f32 v148, v43, v59
	v_cvt_pk_bf16_f32 v149, v91, v75
	v_cvt_pk_bf16_f32 v212, v42, v58
	v_cvt_pk_bf16_f32 v213, v90, v74
	v_max_f32_e32 v214, v214, v214
	v_add_u32_e32 v77, 0x9c00, v186
	v_max_f32_e32 v61, v61, v255
	v_max_f32_e32 v150, v150, v214
	ds_write2_b64 v77, v[148:149], v[212:213] offset0:100 offset1:134
	s_nop 0
	v_mov_b32_dpp v214, v150 quad_perm:[1,0,3,2] row_mask:0xf bank_mask:0xf
	v_sub_f32_e32 v141, v141, v151
	v_mul_f32_e32 v141, 0x3fb8aa3b, v141
	v_exp_f32_e32 v133, v133
	s_waitcnt lgkmcnt(0)
	v_max3_f32 v150, v142, v150, v214
	v_max_f32_dpp v77, v61, v61 row_ror:8 row_mask:0xf bank_mask:0xf
	v_sub_f32_e32 v45, v92, v150
	s_nop 1
	v_mov_b32_dpp v92, v77 row_shl:4 row_mask:0xf bank_mask:0x5
	v_mov_b32_dpp v92, v77 row_shr:4 row_mask:0xf bank_mask:0xa
	v_sub_f32_e32 v60, v60, v150
	v_mul_f32_e32 v60, 0x3fb8aa3b, v60
	v_exp_f32_e32 v61, v60
	v_sub_f32_e32 v60, v76, v150
	v_max_f32_e32 v76, v92, v92
	v_max_f32_e32 v76, v77, v76
	s_nop 1
	v_mov_b32_dpp v92, v76 quad_perm:[2,3,0,1] row_mask:0xf bank_mask:0xf
	v_sub_f32_e32 v44, v44, v150
	v_mul_f32_e32 v44, 0x3fb8aa3b, v44
	v_exp_f32_e32 v77, v44
	v_mul_f32_e32 v60, 0x3fb8aa3b, v60
	v_max_f32_e32 v44, v92, v92
	v_max_f32_e32 v44, v76, v44
	v_exp_f32_e32 v93, v60
	s_nop 1
	v_mov_b32_dpp v60, v44 quad_perm:[1,0,3,2] row_mask:0xf bank_mask:0xf
	v_sub_f32_e32 v142, v142, v150
	v_mul_f32_e32 v76, 0x3fb8aa3b, v142
	v_exp_f32_e32 v142, v76
	v_mul_f32_e32 v45, 0x3fb8aa3b, v45
	v_max3_f32 v149, v143, v44, v60
	v_sub_u32_e32 v44, v96, v181
	v_cmp_gt_u32_e32 vcc, s58, v44
	s_or_b64 vcc, s[2:3], vcc
	v_add_u32_e32 v60, 32, v44
	v_cndmask_b32_e32 v94, v204, v94, vcc
	v_cmp_gt_u32_e32 vcc, s58, v60
	s_or_b64 vcc, s[2:3], vcc
	v_add_u32_e32 v76, 64, v44
	v_cndmask_b32_e32 v62, v204, v62, vcc
	v_cmp_gt_u32_e32 vcc, s58, v76
	s_or_b64 vcc, s[2:3], vcc
	v_add_u32_e32 v44, 0x60, v44
	v_cndmask_b32_e32 v78, v204, v78, vcc
	v_cmp_gt_u32_e32 vcc, s58, v44
	s_or_b64 vcc, s[2:3], vcc
	v_max3_f32 v60, v94, s59, v62
	v_cndmask_b32_e32 v46, v204, v46, vcc
	v_max3_f32 v60, v60, v78, v46
	v_mov_b32_e32 v76, v60
	v_mov_b32_e32 v255, v60
	s_nop 1
	v_permlane16_swap_b32_e32 v76, v255
	v_sub_u32_e32 v96, v96, v182
	v_cmp_gt_u32_e32 vcc, s58, v96
	s_or_b64 vcc, s[2:3], vcc
	v_sub_f32_e32 v92, v217, v149
	v_max_f32_e32 v76, v76, v255
	v_cndmask_b32_e32 v217, v204, v95, vcc
	v_add_u32_e32 v95, 32, v96
	v_cmp_gt_u32_e32 vcc, s58, v95
	s_or_b64 vcc, s[2:3], vcc
	v_add_u32_e32 v95, 64, v96
	v_mul_f32_e32 v60, 0x3fb8aa3b, v92
	v_sub_f32_e32 v92, v218, v149
	v_max_f32_dpp v148, v76, v76 row_ror:8 row_mask:0xf bank_mask:0xf
	v_cndmask_b32_e32 v218, v204, v63, vcc
	v_cmp_gt_u32_e32 vcc, s58, v95
	v_mov_b32_dpp v214, v148 row_shl:4 row_mask:0xf bank_mask:0x5
	v_mov_b32_dpp v214, v148 row_shr:4 row_mask:0xf bank_mask:0xa
	s_or_b64 vcc, s[2:3], vcc
	v_cndmask_b32_e32 v219, v204, v79, vcc
	v_add_u32_e32 v79, 0x60, v96
	v_cmp_gt_u32_e32 vcc, s58, v79
	s_or_b64 vcc, s[2:3], vcc
	v_max3_f32 v63, v217, s59, v218
	v_cndmask_b32_e32 v96, v204, v47, vcc
	v_max_f32_e32 v214, v214, v214
	v_max3_f32 v47, v63, v219, v96
	v_sub_f32_e32 v44, v216, v149
	v_sub_f32_e32 v76, v215, v149
	v_max_f32_e32 v148, v148, v214
	v_mov_b32_e32 v63, v47
	v_mov_b32_e32 v255, v47
	s_nop 1
	v_permlane16_swap_b32_e32 v63, v255
	v_mul_f32_e32 v44, 0x3fb8aa3b, v44
	v_mul_f32_e32 v92, 0x3fb8aa3b, v92
	v_mul_f32_e32 v76, 0x3fb8aa3b, v76
	v_mov_b32_dpp v216, v148 quad_perm:[2,3,0,1] row_mask:0xf bank_mask:0xf
	v_exp_f32_e32 v45, v45
	v_exp_f32_e32 v44, v44
	v_exp_f32_e32 v60, v60
	v_exp_f32_e32 v92, v92
	v_exp_f32_e32 v76, v76
	v_cvt_pk_bf16_f32 v212, v45, v61
	v_cvt_pk_bf16_f32 v213, v93, v77
	v_cvt_pk_bf16_f32 v214, v44, v60
	v_cvt_pk_bf16_f32 v215, v92, v76
	v_max_f32_e32 v216, v216, v216
	v_add_u32_e32 v79, 0xa000, v186
	v_max_f32_e32 v63, v63, v255
	v_max_f32_e32 v148, v148, v216
	ds_write2_b64 v79, v[212:213], v[214:215] offset0:176 offset1:210
	s_nop 0
	v_mov_b32_dpp v216, v148 quad_perm:[1,0,3,2] row_mask:0xf bank_mask:0xf
	v_sub_f32_e32 v143, v143, v149
	v_mul_f32_e32 v143, 0x3fb8aa3b, v143
	v_exp_f32_e32 v135, v135
	s_waitcnt lgkmcnt(0)
	v_max3_f32 v148, v144, v148, v216
	v_max_f32_dpp v79, v63, v63 row_ror:8 row_mask:0xf bank_mask:0xf
	v_sub_f32_e32 v47, v94, v148
	s_nop 1
	v_mov_b32_dpp v94, v79 row_shl:4 row_mask:0xf bank_mask:0x5
	v_mov_b32_dpp v94, v79 row_shr:4 row_mask:0xf bank_mask:0xa
	v_sub_f32_e32 v62, v62, v148
	v_mul_f32_e32 v62, 0x3fb8aa3b, v62
	v_exp_f32_e32 v63, v62
	v_sub_f32_e32 v62, v78, v148
	v_max_f32_e32 v78, v94, v94
	v_max_f32_e32 v78, v79, v78
	s_nop 1
	v_mov_b32_dpp v94, v78 quad_perm:[2,3,0,1] row_mask:0xf bank_mask:0xf
	v_sub_f32_e32 v46, v46, v148
	v_mul_f32_e32 v46, 0x3fb8aa3b, v46
	v_exp_f32_e32 v79, v46
	v_mul_f32_e32 v62, 0x3fb8aa3b, v62
	v_max_f32_e32 v46, v94, v94
	v_max_f32_e32 v46, v78, v46
	v_exp_f32_e32 v95, v62
	s_nop 1
	v_mov_b32_dpp v62, v46 quad_perm:[1,0,3,2] row_mask:0xf bank_mask:0xf
	v_sub_f32_e32 v144, v144, v148
	v_mul_f32_e32 v78, 0x3fb8aa3b, v144
	v_exp_f32_e32 v144, v78
	v_mul_f32_e32 v47, 0x3fb8aa3b, v47
	v_max3_f32 v147, v145, v46, v62
	v_sub_f32_e32 v78, v219, v147
	v_mul_f32_e32 v78, 0x3fb8aa3b, v78
	v_sub_f32_e32 v46, v217, v147
	v_sub_f32_e32 v62, v218, v147
	v_exp_f32_e32 v94, v78
	v_sub_f32_e32 v78, v96, v147
	v_sub_f32_e32 v145, v145, v147
	v_mul_f32_e32 v46, 0x3fb8aa3b, v46
	v_mul_f32_e32 v62, 0x3fb8aa3b, v62
	v_mul_f32_e32 v78, 0x3fb8aa3b, v78
	v_exp_f32_e32 v47, v47
	v_exp_f32_e32 v46, v46
	v_exp_f32_e32 v62, v62
	v_exp_f32_e32 v78, v78
	v_mul_f32_e32 v96, 0x3fb8aa3b, v145
	v_exp_f32_e32 v137, v137
	v_exp_f32_e32 v139, v139
	v_exp_f32_e32 v141, v141
	v_exp_f32_e32 v143, v143
	v_exp_f32_e32 v145, v96
	v_cvt_pk_bf16_f32 v208, v47, v63
	v_cvt_pk_bf16_f32 v209, v95, v79
	v_cvt_pk_bf16_f32 v210, v46, v62
	v_cvt_pk_bf16_f32 v211, v94, v78
	v_add_u32_e32 v96, 0xa400, v186
	ds_write2_b64 v96, v[208:209], v[210:211] offset0:116 offset1:150
	v_pk_mul_f32 v[14:15], v[14:15], v[144:145]
	v_pk_mul_f32 v[12:13], v[12:13], v[142:143]
	v_pk_mul_f32 v[10:11], v[10:11], v[140:141]
	v_pk_mul_f32 v[8:9], v[8:9], v[138:139]
	v_pk_mul_f32 v[6:7], v[6:7], v[136:137]
	v_pk_mul_f32 v[4:5], v[4:5], v[134:135]
	v_pk_mul_f32 v[2:3], v[2:3], v[132:133]
	v_pk_mul_f32 v[0:1], v[0:1], v[130:131]
	v_pk_mul_f32 v[30:31], v[30:31], v[144:145]
	v_pk_mul_f32 v[28:29], v[28:29], v[142:143]
	v_pk_mul_f32 v[26:27], v[26:27], v[140:141]
	v_pk_mul_f32 v[24:25], v[24:25], v[138:139]
	v_pk_mul_f32 v[22:23], v[22:23], v[136:137]
	v_pk_mul_f32 v[20:21], v[20:21], v[134:135]
	v_pk_mul_f32 v[18:19], v[18:19], v[132:133]
	v_pk_mul_f32 v[16:17], v[16:17], v[130:131]
	s_mov_b32 s2, -16
	v_mov_b32_e32 v96, v185
	v_mov_b32_e32 v208, v184

.LBB0_718:
	ds_read_b128 v[210:213], v96
	ds_read_b128 v[214:217], v208
	s_add_i32 s2, s2, 32
	s_cmpk_lt_u32 s2, 0x70
	s_waitcnt lgkmcnt(0)
	v_mfma_f32_32x32x16_bf16 v[0:15], v[210:213], v[214:217], v[0:15]
	ds_read_b128 v[214:217], v208 offset:8704
	s_waitcnt lgkmcnt(0)
	v_mfma_f32_32x32x16_bf16 v[16:31], v[210:213], v[214:217], v[16:31]
	ds_read_b128 v[210:213], v96 offset:32
	ds_read_b128 v[214:217], v208 offset:32
	v_add_u32_e32 v96, 64, v96
	s_waitcnt lgkmcnt(0)
	v_mfma_f32_32x32x16_bf16 v[0:15], v[210:213], v[214:217], v[0:15]
	ds_read_b128 v[214:217], v208 offset:8736
	v_add_u32_e32 v208, 64, v208
	s_waitcnt lgkmcnt(0)
	v_mfma_f32_32x32x16_bf16 v[16:31], v[210:213], v[214:217], v[16:31]
	s_cbranch_scc1 .LBB0_718
	v_pk_add_f32 v[32:33], v[32:33], 0 op_sel_hi:[1,0]
	v_mov_b32_e32 v208, v131
	v_pk_add_f32 v[32:33], v[48:49], v[32:33]
	v_mov_b32_e32 v209, v130
	v_pk_add_f32 v[32:33], v[80:81], v[32:33]
	v_mov_b32_e32 v130, v133
	v_pk_add_f32 v[32:33], v[64:65], v[32:33]
	v_mov_b32_e32 v131, v132
	v_pk_fma_f32 v[128:129], v[128:129], v[208:209], v[32:33]
	v_pk_add_f32 v[32:33], v[34:35], 0 op_sel_hi:[1,0]
	v_mov_b32_e32 v132, v135
	v_pk_add_f32 v[32:33], v[50:51], v[32:33]
	v_mov_b32_e32 v133, v134
	v_pk_add_f32 v[32:33], v[82:83], v[32:33]
	v_mov_b32_e32 v134, v137
	v_pk_add_f32 v[32:33], v[66:67], v[32:33]
	v_mov_b32_e32 v135, v136
	v_pk_fma_f32 v[126:127], v[126:127], v[130:131], v[32:33]
	v_pk_add_f32 v[32:33], v[36:37], 0 op_sel_hi:[1,0]
	v_mov_b32_e32 v136, v139
	v_pk_add_f32 v[32:33], v[52:53], v[32:33]
	v_mov_b32_e32 v137, v138
	v_pk_add_f32 v[32:33], v[84:85], v[32:33]
	v_mov_b32_e32 v138, v141
	v_pk_add_f32 v[32:33], v[68:69], v[32:33]
	v_mov_b32_e32 v139, v140
	v_pk_fma_f32 v[124:125], v[124:125], v[132:133], v[32:33]
	v_pk_add_f32 v[32:33], v[38:39], 0 op_sel_hi:[1,0]
	v_mov_b32_e32 v140, v143
	v_pk_add_f32 v[32:33], v[54:55], v[32:33]
	v_mov_b32_e32 v141, v142
	v_pk_add_f32 v[32:33], v[86:87], v[32:33]
	v_mov_b32_e32 v142, v145
	v_pk_add_f32 v[32:33], v[70:71], v[32:33]
	v_mov_b32_e32 v143, v144
	v_pk_fma_f32 v[122:123], v[122:123], v[134:135], v[32:33]
	v_pk_add_f32 v[32:33], v[40:41], 0 op_sel_hi:[1,0]
	v_pk_add_f32 v[32:33], v[56:57], v[32:33]
	v_pk_add_f32 v[32:33], v[88:89], v[32:33]
	v_pk_add_f32 v[32:33], v[72:73], v[32:33]
	v_pk_fma_f32 v[120:121], v[120:121], v[136:137], v[32:33]
	v_pk_add_f32 v[32:33], v[42:43], 0 op_sel_hi:[1,0]
	v_pk_add_f32 v[32:33], v[58:59], v[32:33]
	v_pk_add_f32 v[32:33], v[90:91], v[32:33]
	v_pk_add_f32 v[32:33], v[74:75], v[32:33]
	v_pk_fma_f32 v[118:119], v[118:119], v[138:139], v[32:33]
	v_pk_add_f32 v[32:33], v[44:45], 0 op_sel_hi:[1,0]
	v_pk_add_f32 v[32:33], v[60:61], v[32:33]
	v_pk_add_f32 v[32:33], v[92:93], v[32:33]
	v_pk_add_f32 v[32:33], v[76:77], v[32:33]
	v_pk_fma_f32 v[116:117], v[116:117], v[140:141], v[32:33]
	v_pk_add_f32 v[32:33], v[46:47], 0 op_sel_hi:[1,0]
	v_pk_add_f32 v[32:33], v[62:63], v[32:33]
	v_pk_add_f32 v[32:33], v[94:95], v[32:33]
	v_pk_add_f32 v[32:33], v[78:79], v[32:33]
	v_pk_fma_f32 v[114:115], v[114:115], v[142:143], v[32:33]
	s_add_i32 s53, s53, 1
	s_cmp_lg_u32 s53, 5
	s_cbranch_scc1 .LBB0_721
	s_branch .LBB0_722

.Latt_nm:
	s_nop 7
	s_nop 7
	s_nop 7
	s_add_i32 s6, s53, s49
	v_mbcnt_hi_u32_b32 v148, -1, v195
	v_lshl_add_u32 v96, s6, 7, v183
	v_and_b32_e32 v147, 64, v148
	v_add_u32_e32 v149, 64, v147
	v_xor_b32_e32 v147, 16, v148
	v_cmp_lt_i32_e32 vcc, v147, v149
	v_max3_f32 v150, v80, s59, v48
	v_max3_f32 v150, v150, v64, v32
	v_mov_b32_e32 v151, v150
	v_mov_b32_e32 v255, v150
	s_nop 1
	v_permlane16_swap_b32_e32 v151, v255
	v_add_u32_e32 v187, 0x8800, v186
	v_add_u32_e32 v215, 0x9000, v186
	v_max_f32_e32 v150, v151, v255
	v_xor_b32_e32 v151, 8, v148
	v_cmp_lt_i32_e32 vcc, v151, v149
	s_nop 1
	v_cndmask_b32_e32 v151, v148, v151, vcc
	v_max_f32_dpp v150, v150, v150 row_ror:8 row_mask:0xf bank_mask:0xf
	v_xor_b32_e32 v151, 4, v148
	v_cmp_lt_i32_e32 vcc, v151, v149
	s_nop 1
	v_cndmask_b32_e32 v151, v148, v151, vcc
	s_nop 1
	v_mov_b32_dpp v151, v150 row_shl:4 row_mask:0xf bank_mask:0x5
	s_nop 1
	v_mov_b32_dpp v151, v150 row_shr:4 row_mask:0xf bank_mask:0xa
	v_max_f32_e32 v150, v150, v151
	v_xor_b32_e32 v151, 2, v148
	v_cmp_lt_i32_e32 vcc, v151, v149
	s_nop 1
	v_cndmask_b32_e32 v151, v148, v151, vcc
	v_max_f32_dpp v150, v150, v150 quad_perm:[2,3,0,1] row_mask:0xf bank_mask:0xf
	v_xor_b32_e32 v151, 1, v148
	v_cmp_lt_i32_e32 vcc, v151, v149
	v_sub_u32_e32 v149, v96, v161
	s_nop 0
	v_cndmask_b32_e32 v148, v148, v151, vcc
	v_mov_b32_e32 v151, v81
	v_mov_b32_e32 v152, v49
	v_max3_f32 v49, v151, s59, v152
	v_mov_b32_e32 v153, v65
	v_add_u32_e32 v65, 0x60, v149
	v_mov_b32_dpp v148, v150 quad_perm:[1,0,3,2] row_mask:0xf bank_mask:0xf
	v_mov_b32_e32 v154, v33
	v_max3_f32 v33, v49, v153, v154
	v_mov_b32_e32 v49, v33
	v_mov_b32_e32 v255, v33
	s_nop 1
	v_permlane16_swap_b32_e32 v49, v255
	v_max3_f32 v207, v130, v150, v148
	v_sub_f32_e32 v48, v48, v207
	v_mul_f32_e32 v48, 0x3fb8aa3b, v48
	v_max_f32_e32 v49, v49, v255
	v_sub_f32_e32 v33, v80, v207
	v_sub_f32_e32 v32, v32, v207
	v_mul_f32_e32 v32, 0x3fb8aa3b, v32
	v_sub_f32_e32 v130, v130, v207
	v_max_f32_dpp v65, v49, v49 row_ror:8 row_mask:0xf bank_mask:0xf
	s_nop 1
	v_mov_b32_dpp v80, v65 row_shl:4 row_mask:0xf bank_mask:0x5
	s_nop 1
	v_mov_b32_dpp v80, v65 row_shr:4 row_mask:0xf bank_mask:0xa
	v_exp_f32_e32 v49, v48
	v_sub_f32_e32 v48, v64, v207
	v_mul_f32_e32 v48, 0x3fb8aa3b, v48
	v_exp_f32_e32 v81, v48
	v_max_f32_e32 v64, v80, v80
	v_max_f32_e32 v64, v65, v64
	s_nop 1
	v_mov_b32_dpp v80, v64 quad_perm:[2,3,0,1] row_mask:0xf bank_mask:0xf
	v_exp_f32_e32 v65, v32
	v_mul_f32_e32 v33, 0x3fb8aa3b, v33
	v_exp_f32_e32 v33, v33
	v_max_f32_e32 v32, v80, v80
	v_max_f32_e32 v32, v64, v32
	s_nop 1
	v_mov_b32_dpp v48, v32 quad_perm:[1,0,3,2] row_mask:0xf bank_mask:0xf
	v_mul_f32_e32 v64, 0x3fb8aa3b, v130
	v_exp_f32_e32 v130, v64
	v_cvt_pk_bf16_f32 v148, v33, v49
	v_cvt_pk_bf16_f32 v149, v81, v65
	v_max3_f32 v206, v131, v32, v48
	v_max3_f32 v48, v82, s59, v50
	v_max3_f32 v48, v48, v66, v34
	v_mov_b32_e32 v64, v48
	v_mov_b32_e32 v255, v48
	s_nop 1
	v_permlane16_swap_b32_e32 v64, v255
	v_sub_f32_e32 v32, v151, v206
	v_sub_f32_e32 v80, v152, v206
	v_mul_f32_e32 v32, 0x3fb8aa3b, v32
	v_exp_f32_e32 v32, v32
	v_max_f32_e32 v64, v64, v255
	v_mul_f32_e32 v48, 0x3fb8aa3b, v80
	v_sub_f32_e32 v80, v153, v206
	v_mul_f32_e32 v80, 0x3fb8aa3b, v80
	v_exp_f32_e32 v48, v48
	v_max_f32_dpp v150, v64, v64 row_ror:8 row_mask:0xf bank_mask:0xf
	v_sub_f32_e32 v64, v154, v206
	v_sub_u32_e32 v154, v96, v170
	v_mov_b32_dpp v151, v150 row_shl:4 row_mask:0xf bank_mask:0x5
	s_nop 1
	v_mov_b32_dpp v151, v150 row_shr:4 row_mask:0xf bank_mask:0xa
	v_mov_b32_e32 v155, v83
	v_mov_b32_e32 v156, v51
	v_max3_f32 v51, v155, s59, v156
	v_mov_b32_e32 v160, v67
	v_add_u32_e32 v67, 0x60, v154
	v_max_f32_e32 v151, v151, v151
	v_mov_b32_e32 v154, v35
	v_max3_f32 v35, v51, v160, v154
	v_max_f32_e32 v152, v150, v151
	v_mov_b32_e32 v51, v35
	v_mov_b32_e32 v255, v35
	s_nop 1
	v_permlane16_swap_b32_e32 v51, v255
	v_mov_b32_dpp v153, v152 quad_perm:[2,3,0,1] row_mask:0xf bank_mask:0xf
	v_mul_f32_e32 v64, 0x3fb8aa3b, v64
	v_exp_f32_e32 v80, v80
	v_exp_f32_e32 v64, v64
	v_max_f32_e32 v153, v153, v153
	v_max_f32_e32 v51, v51, v255
	v_max_f32_e32 v152, v152, v153
	s_nop 1
	v_mov_b32_dpp v153, v152 quad_perm:[1,0,3,2] row_mask:0xf bank_mask:0xf
	v_cvt_pk_bf16_f32 v150, v32, v48
	v_cvt_pk_bf16_f32 v151, v80, v64
	ds_write2_b64 v187, v[148:149], v[150:151] offset0:128 offset1:162
	v_max3_f32 v189, v132, v152, v153
	v_max_f32_dpp v67, v51, v51 row_ror:8 row_mask:0xf bank_mask:0xf
	v_sub_f32_e32 v35, v82, v189
	s_nop 1
	v_mov_b32_dpp v82, v67 row_shl:4 row_mask:0xf bank_mask:0x5
	s_nop 1
	v_mov_b32_dpp v82, v67 row_shr:4 row_mask:0xf bank_mask:0xa
	v_sub_f32_e32 v50, v50, v189
	v_mul_f32_e32 v50, 0x3fb8aa3b, v50
	v_exp_f32_e32 v51, v50
	v_sub_f32_e32 v50, v66, v189
	s_waitcnt lgkmcnt(0)
	v_max_f32_e32 v66, v82, v82
	v_max_f32_e32 v66, v67, v66
	s_nop 1
	v_mov_b32_dpp v82, v66 quad_perm:[2,3,0,1] row_mask:0xf bank_mask:0xf
	v_sub_f32_e32 v34, v34, v189
	v_mul_f32_e32 v34, 0x3fb8aa3b, v34
	v_exp_f32_e32 v67, v34
	v_mul_f32_e32 v50, 0x3fb8aa3b, v50
	v_max_f32_e32 v34, v82, v82
	v_max_f32_e32 v34, v66, v34
	v_exp_f32_e32 v83, v50
	s_nop 1
	v_mov_b32_dpp v50, v34 quad_perm:[1,0,3,2] row_mask:0xf bank_mask:0xf
	v_sub_f32_e32 v132, v132, v189
	v_mul_f32_e32 v66, 0x3fb8aa3b, v132
	v_exp_f32_e32 v132, v66
	v_mul_f32_e32 v35, 0x3fb8aa3b, v35
	v_max3_f32 v188, v133, v34, v50
	v_sub_u32_e32 v34, v96, v171
	v_add_u32_e32 v66, 64, v34
	v_max3_f32 v50, v84, s59, v52
	v_mov_b32_e32 v150, v36
	v_max3_f32 v34, v50, v68, v150
	v_mov_b32_e32 v36, v34
	v_mov_b32_e32 v255, v34
	s_nop 1
	v_permlane16_swap_b32_e32 v36, v255
	v_sub_f32_e32 v151, v154, v188
	v_sub_f32_e32 v50, v133, v188
	v_mul_f32_e32 v133, 0x3fb8aa3b, v50
	v_sub_f32_e32 v50, v155, v188
	v_max_f32_e32 v36, v36, v255
	s_nop 1
	v_mov_b32_dpp v66, v36 row_ror:8 row_mask:0xf bank_mask:0xf
	v_mul_f32_e32 v50, 0x3fb8aa3b, v50
	v_exp_f32_e32 v34, v50
	v_sub_f32_e32 v50, v156, v188
	v_sub_f32_e32 v82, v160, v188
	v_max_f32_e32 v66, v66, v66
	v_max_f32_e32 v36, v36, v66
	s_nop 1
	v_mov_b32_dpp v66, v36 row_shl:4 row_mask:0xf bank_mask:0x5
	s_nop 1
	v_mov_b32_dpp v66, v36 row_shr:4 row_mask:0xf bank_mask:0xa
	v_mul_f32_e32 v50, 0x3fb8aa3b, v50
	v_mul_f32_e32 v82, 0x3fb8aa3b, v82
	v_exp_f32_e32 v35, v35
	v_exp_f32_e32 v50, v50
	v_max_f32_e32 v66, v66, v66
	v_max_f32_e32 v152, v36, v66
	s_nop 1
	v_mov_b32_dpp v153, v152 quad_perm:[2,3,0,1] row_mask:0xf bank_mask:0xf
	v_mul_f32_e32 v36, 0x3fb8aa3b, v151
	v_exp_f32_e32 v82, v82
	v_exp_f32_e32 v66, v36
	v_cvt_pk_bf16_f32 v148, v35, v51
	v_max_f32_e32 v151, v153, v153
	v_cvt_pk_bf16_f32 v149, v83, v67
	v_mov_b32_e32 v154, v85
	v_mov_b32_e32 v155, v53
	v_max3_f32 v53, v154, s59, v155
	v_mov_b32_e32 v156, v69
	v_cvt_pk_bf16_f32 v36, v34, v50
	v_mov_b32_e32 v153, v37
	v_max3_f32 v53, v53, v156, v153
	v_mov_b32_e32 v69, v53
	v_mov_b32_e32 v255, v53
	s_nop 1
	v_permlane16_swap_b32_e32 v69, v255
	s_nop 1
	v_mov_b32_dpp v69, v255 quad_perm:[0,1,2,3] row_mask:0x5 bank_mask:0xf
	v_cvt_pk_bf16_f32 v37, v82, v66
	ds_write2_b64 v187, v[148:149], v[36:37] offset0:196 offset1:230
	v_max_f32_e32 v151, v152, v151
	s_nop 1
	v_mov_b32_dpp v152, v151 quad_perm:[1,0,3,2] row_mask:0xf bank_mask:0xf
	v_max_f32_e32 v37, v69, v69
	v_max_f32_e32 v53, v53, v37
	v_sub_f32_e32 v131, v131, v206
	s_waitcnt lgkmcnt(0)
	v_max3_f32 v187, v134, v151, v152
	v_sub_f32_e32 v37, v84, v187
	v_sub_f32_e32 v52, v52, v187
	v_max_f32_dpp v69, v53, v53 row_ror:8 row_mask:0xf bank_mask:0xf
	s_nop 1
	v_mov_b32_dpp v84, v69 row_shl:4 row_mask:0xf bank_mask:0x5
	s_nop 1
	v_mov_b32_dpp v84, v69 row_shr:4 row_mask:0xf bank_mask:0xa
	v_mul_f32_e32 v52, 0x3fb8aa3b, v52
	v_exp_f32_e32 v53, v52
	v_sub_f32_e32 v52, v68, v187
	v_mul_f32_e32 v52, 0x3fb8aa3b, v52
	v_max_f32_e32 v68, v84, v84
	v_max_f32_e32 v68, v69, v68
	s_nop 1
	v_mov_b32_dpp v84, v68 quad_perm:[2,3,0,1] row_mask:0xf bank_mask:0xf
	v_exp_f32_e32 v85, v52
	v_sub_f32_e32 v52, v150, v187
	v_mul_f32_e32 v52, 0x3fb8aa3b, v52
	v_exp_f32_e32 v69, v52
	v_max_f32_e32 v52, v84, v84
	v_max_f32_e32 v52, v68, v52
	s_nop 1
	v_mov_b32_dpp v68, v52 quad_perm:[1,0,3,2] row_mask:0xf bank_mask:0xf
	v_sub_f32_e32 v36, v134, v187
	v_mul_f32_e32 v36, 0x3fb8aa3b, v36
	v_exp_f32_e32 v134, v36
	v_max3_f32 v160, v135, v52, v68
	v_max3_f32 v52, v86, s59, v54
	v_max3_f32 v52, v52, v70, v38
	v_mov_b32_e32 v68, v52
	v_mov_b32_e32 v255, v52
	s_nop 1
	v_permlane16_swap_b32_e32 v68, v255
	v_sub_f32_e32 v36, v154, v160
	v_sub_u32_e32 v154, v96, v174
	v_max_f32_e32 v68, v68, v255
	s_nop 1
	v_mov_b32_e32 v212, v87
	v_max_f32_dpp v150, v68, v68 row_ror:8 row_mask:0xf bank_mask:0xf
	v_mov_b32_e32 v213, v55
	s_nop 0
	v_mov_b32_dpp v151, v150 row_shl:4 row_mask:0xf bank_mask:0x5
	s_nop 1
	v_mov_b32_dpp v151, v150 row_shr:4 row_mask:0xf bank_mask:0xa
	v_mov_b32_e32 v214, v71
	v_add_u32_e32 v71, 0x60, v154
	v_max3_f32 v55, v212, s59, v213
	v_mov_b32_e32 v154, v39
	v_max_f32_e32 v151, v151, v151
	v_max3_f32 v39, v55, v214, v154
	v_max_f32_e32 v152, v150, v151
	v_mov_b32_e32 v55, v39
	v_mov_b32_e32 v255, v39
	s_nop 1
	v_permlane16_swap_b32_e32 v55, v255
	v_sub_f32_e32 v68, v153, v160
	v_mov_b32_dpp v153, v152 quad_perm:[2,3,0,1] row_mask:0xf bank_mask:0xf
	v_sub_f32_e32 v84, v155, v160
	v_mul_f32_e32 v52, 0x3fb8aa3b, v84
	v_max_f32_e32 v55, v55, v255
	v_max_f32_e32 v153, v153, v153
	v_max_f32_e32 v152, v152, v153
	s_nop 0
	s_nop 1
	v_mov_b32_dpp v153, v152 quad_perm:[1,0,3,2] row_mask:0xf bank_mask:0xf
	v_sub_f32_e32 v84, v156, v160
	v_mul_f32_e32 v37, 0x3fb8aa3b, v37
	v_mul_f32_e32 v36, 0x3fb8aa3b, v36
	v_max3_f32 v156, v136, v152, v153
	v_max_f32_dpp v71, v55, v55 row_ror:8 row_mask:0xf bank_mask:0xf
	v_sub_f32_e32 v39, v86, v156
	s_nop 1
	v_mov_b32_dpp v86, v71 row_shl:4 row_mask:0xf bank_mask:0x5
	s_nop 1
	v_mov_b32_dpp v86, v71 row_shr:4 row_mask:0xf bank_mask:0xa
	v_sub_f32_e32 v54, v54, v156
	v_mul_f32_e32 v54, 0x3fb8aa3b, v54
	v_exp_f32_e32 v55, v54
	v_sub_f32_e32 v54, v70, v156
	v_max_f32_e32 v70, v86, v86
	v_max_f32_e32 v70, v71, v70
	s_nop 1
	v_mov_b32_dpp v86, v70 quad_perm:[2,3,0,1] row_mask:0xf bank_mask:0xf
	v_sub_f32_e32 v38, v38, v156
	v_mul_f32_e32 v38, 0x3fb8aa3b, v38
	v_exp_f32_e32 v71, v38
	v_mul_f32_e32 v54, 0x3fb8aa3b, v54
	v_max_f32_e32 v38, v86, v86
	v_max_f32_e32 v38, v70, v38
	v_exp_f32_e32 v87, v54
	s_nop 1
	v_mov_b32_dpp v54, v38 quad_perm:[1,0,3,2] row_mask:0xf bank_mask:0xf
	v_sub_f32_e32 v136, v136, v156
	v_mul_f32_e32 v84, 0x3fb8aa3b, v84
	v_mul_f32_e32 v68, 0x3fb8aa3b, v68
	v_mul_f32_e32 v70, 0x3fb8aa3b, v136
	v_max3_f32 v155, v137, v38, v54
	v_sub_u32_e32 v38, v96, v175
	v_exp_f32_e32 v37, v37
	v_exp_f32_e32 v36, v36
	v_exp_f32_e32 v52, v52
	v_exp_f32_e32 v84, v84
	v_exp_f32_e32 v68, v68
	v_exp_f32_e32 v136, v70
	v_add_u32_e32 v70, 64, v38
	v_cvt_pk_bf16_f32 v148, v37, v53
	v_cvt_pk_bf16_f32 v149, v85, v69
	v_cvt_pk_bf16_f32 v150, v36, v52
	v_cvt_pk_bf16_f32 v151, v84, v68
	ds_write2_b64 v215, v[148:149], v[150:151] offset0:144 offset1:178
	v_max3_f32 v54, v88, s59, v56
	v_mov_b32_e32 v150, v40
	v_max3_f32 v38, v54, v72, v150
	v_mov_b32_e32 v40, v38
	v_mov_b32_e32 v255, v38
	s_nop 1
	v_permlane16_swap_b32_e32 v40, v255
	v_sub_f32_e32 v151, v154, v155
	v_sub_f32_e32 v54, v137, v155
	v_mul_f32_e32 v137, 0x3fb8aa3b, v54
	v_sub_f32_e32 v54, v212, v155
	s_waitcnt lgkmcnt(0)
	v_max_f32_e32 v40, v40, v255
	s_nop 1
	v_mov_b32_dpp v70, v40 row_ror:8 row_mask:0xf bank_mask:0xf
	v_mul_f32_e32 v54, 0x3fb8aa3b, v54
	v_exp_f32_e32 v38, v54
	v_sub_f32_e32 v54, v213, v155
	v_sub_f32_e32 v86, v214, v155
	v_max_f32_e32 v70, v70, v70
	v_max_f32_e32 v40, v40, v70
	s_nop 1
	v_mov_b32_dpp v70, v40 row_shl:4 row_mask:0xf bank_mask:0x5
	s_nop 1
	v_mov_b32_dpp v70, v40 row_shr:4 row_mask:0xf bank_mask:0xa
	v_mul_f32_e32 v39, 0x3fb8aa3b, v39
	v_mul_f32_e32 v54, 0x3fb8aa3b, v54
	v_mul_f32_e32 v86, 0x3fb8aa3b, v86
	v_exp_f32_e32 v39, v39
	v_max_f32_e32 v70, v70, v70
	v_max_f32_e32 v152, v40, v70
	s_nop 1
	v_mov_b32_dpp v153, v152 quad_perm:[2,3,0,1] row_mask:0xf bank_mask:0xf
	v_mul_f32_e32 v40, 0x3fb8aa3b, v151
	v_exp_f32_e32 v54, v54
	v_exp_f32_e32 v86, v86
	v_exp_f32_e32 v70, v40
	v_max_f32_e32 v151, v153, v153
	v_cvt_pk_bf16_f32 v148, v39, v55
	v_mov_b32_e32 v212, v89
	v_mov_b32_e32 v213, v57
	v_max3_f32 v57, v212, s59, v213
	v_mov_b32_e32 v214, v73
	v_cvt_pk_bf16_f32 v149, v87, v71
	v_mov_b32_e32 v216, v41
	v_max3_f32 v57, v57, v214, v216
	v_mov_b32_e32 v73, v57
	v_mov_b32_e32 v255, v57
	s_nop 1
	v_permlane16_swap_b32_e32 v73, v255
	s_nop 1
	v_mov_b32_dpp v73, v255 quad_perm:[0,1,2,3] row_mask:0x5 bank_mask:0xf
	v_cvt_pk_bf16_f32 v40, v38, v54
	v_cvt_pk_bf16_f32 v41, v86, v70
	ds_write2_b64 v215, v[148:149], v[40:41] offset0:212 offset1:246
	v_max_f32_e32 v151, v152, v151
	v_max_f32_e32 v41, v73, v73
	v_max_f32_e32 v57, v57, v41
	v_mov_b32_dpp v152, v151 quad_perm:[1,0,3,2] row_mask:0xf bank_mask:0xf
	v_sub_f32_e32 v135, v135, v160
	v_mul_f32_e32 v131, 0x3fb8aa3b, v131
	v_mul_f32_e32 v135, 0x3fb8aa3b, v135
	s_waitcnt lgkmcnt(0)
	v_max3_f32 v154, v138, v151, v152
	v_max_f32_dpp v73, v57, v57 row_ror:8 row_mask:0xf bank_mask:0xf
	v_sub_f32_e32 v41, v88, v154
	s_nop 1
	v_mov_b32_dpp v88, v73 row_shl:4 row_mask:0xf bank_mask:0x5
	s_nop 1
	v_mov_b32_dpp v88, v73 row_shr:4 row_mask:0xf bank_mask:0xa
	v_sub_f32_e32 v56, v56, v154
	v_mul_f32_e32 v56, 0x3fb8aa3b, v56
	v_exp_f32_e32 v57, v56
	v_sub_f32_e32 v56, v72, v154
	v_max_f32_e32 v72, v88, v88
	v_max_f32_e32 v72, v73, v72
	s_nop 1
	v_mov_b32_dpp v88, v72 quad_perm:[2,3,0,1] row_mask:0xf bank_mask:0xf
	v_mul_f32_e32 v56, 0x3fb8aa3b, v56
	v_exp_f32_e32 v89, v56
	v_sub_f32_e32 v56, v150, v154
	v_mul_f32_e32 v56, 0x3fb8aa3b, v56
	v_exp_f32_e32 v73, v56
	v_max_f32_e32 v56, v88, v88
	v_max_f32_e32 v56, v72, v56
	s_nop 1
	v_mov_b32_dpp v72, v56 quad_perm:[1,0,3,2] row_mask:0xf bank_mask:0xf
	v_sub_f32_e32 v40, v138, v154
	v_mul_f32_e32 v40, 0x3fb8aa3b, v40
	v_exp_f32_e32 v138, v40
	v_max3_f32 v153, v139, v56, v72
	v_max3_f32 v56, v90, s59, v58
	v_max3_f32 v56, v56, v74, v42
	v_mov_b32_e32 v72, v56
	v_mov_b32_e32 v255, v56
	s_nop 1
	v_permlane16_swap_b32_e32 v72, v255
	v_sub_f32_e32 v88, v213, v153
	v_max_f32_e32 v72, v72, v255
	v_mul_f32_e32 v56, 0x3fb8aa3b, v88
	v_sub_f32_e32 v88, v214, v153
	v_mov_b32_e32 v214, v91
	v_max_f32_dpp v150, v72, v72 row_ror:8 row_mask:0xf bank_mask:0xf
	v_mov_b32_e32 v215, v59
	s_nop 0
	v_mov_b32_dpp v151, v150 row_shl:4 row_mask:0xf bank_mask:0x5
	s_nop 1
	v_mov_b32_dpp v151, v150 row_shr:4 row_mask:0xf bank_mask:0xa
	v_sub_f32_e32 v72, v216, v153
	v_mov_b32_e32 v216, v75
	v_max3_f32 v59, v214, s59, v215
	v_mov_b32_e32 v213, v43
	v_max_f32_e32 v151, v151, v151
	v_max3_f32 v43, v59, v216, v213
	v_sub_f32_e32 v40, v212, v153
	v_max_f32_e32 v152, v150, v151
	v_mov_b32_e32 v59, v43
	v_mov_b32_e32 v255, v43
	s_nop 1
	v_permlane16_swap_b32_e32 v59, v255
	v_mul_f32_e32 v41, 0x3fb8aa3b, v41
	v_mul_f32_e32 v40, 0x3fb8aa3b, v40
	v_mul_f32_e32 v88, 0x3fb8aa3b, v88
	v_mul_f32_e32 v72, 0x3fb8aa3b, v72
	v_mov_b32_dpp v212, v152 quad_perm:[2,3,0,1] row_mask:0xf bank_mask:0xf
	v_exp_f32_e32 v41, v41
	v_exp_f32_e32 v40, v40
	v_exp_f32_e32 v56, v56
	v_exp_f32_e32 v88, v88
	v_exp_f32_e32 v72, v72
	v_cvt_pk_bf16_f32 v148, v41, v57
	v_cvt_pk_bf16_f32 v149, v89, v73
	v_cvt_pk_bf16_f32 v150, v40, v56
	v_cvt_pk_bf16_f32 v151, v88, v72
	v_max_f32_e32 v212, v212, v212
	v_add_u32_e32 v75, 0x9800, v186
	v_max_f32_e32 v59, v59, v255
	v_max_f32_e32 v152, v152, v212
	ds_write2_b64 v75, v[148:149], v[150:151] offset0:160 offset1:194
	s_nop 0
	v_mov_b32_dpp v212, v152 quad_perm:[1,0,3,2] row_mask:0xf bank_mask:0xf
	v_sub_f32_e32 v139, v139, v153
	v_mul_f32_e32 v139, 0x3fb8aa3b, v139
	v_exp_f32_e32 v131, v131
	s_waitcnt lgkmcnt(0)
	v_max3_f32 v152, v140, v152, v212
	v_max_f32_dpp v75, v59, v59 row_ror:8 row_mask:0xf bank_mask:0xf
	v_sub_f32_e32 v43, v90, v152
	s_nop 1
	v_mov_b32_dpp v90, v75 row_shl:4 row_mask:0xf bank_mask:0x5
	s_nop 1
	v_mov_b32_dpp v90, v75 row_shr:4 row_mask:0xf bank_mask:0xa
	v_sub_f32_e32 v58, v58, v152
	v_mul_f32_e32 v58, 0x3fb8aa3b, v58
	v_exp_f32_e32 v59, v58
	v_sub_f32_e32 v58, v74, v152
	v_max_f32_e32 v74, v90, v90
	v_max_f32_e32 v74, v75, v74
	s_nop 1
	v_mov_b32_dpp v90, v74 quad_perm:[2,3,0,1] row_mask:0xf bank_mask:0xf
	v_sub_f32_e32 v42, v42, v152
	v_mul_f32_e32 v42, 0x3fb8aa3b, v42
	v_exp_f32_e32 v75, v42
	v_mul_f32_e32 v58, 0x3fb8aa3b, v58
	v_max_f32_e32 v42, v90, v90
	v_max_f32_e32 v42, v74, v42
	v_exp_f32_e32 v91, v58
	s_nop 1
	v_mov_b32_dpp v58, v42 quad_perm:[1,0,3,2] row_mask:0xf bank_mask:0xf
	v_sub_f32_e32 v140, v140, v152
	v_mul_f32_e32 v74, 0x3fb8aa3b, v140
	v_exp_f32_e32 v140, v74
	v_mul_f32_e32 v43, 0x3fb8aa3b, v43
	v_max3_f32 v151, v141, v42, v58
	v_max3_f32 v58, v92, s59, v60
	v_max3_f32 v58, v58, v76, v44
	v_mov_b32_e32 v74, v58
	v_mov_b32_e32 v255, v58
	s_nop 1
	v_permlane16_swap_b32_e32 v74, v255
	v_sub_f32_e32 v90, v215, v151
	v_max_f32_e32 v74, v74, v255
	v_mul_f32_e32 v58, 0x3fb8aa3b, v90
	v_sub_f32_e32 v90, v216, v151
	v_mov_b32_e32 v216, v93
	v_max_f32_dpp v150, v74, v74 row_ror:8 row_mask:0xf bank_mask:0xf
	v_mov_b32_e32 v217, v61
	s_nop 0
	v_mov_b32_dpp v212, v150 row_shl:4 row_mask:0xf bank_mask:0x5
	s_nop 1
	v_mov_b32_dpp v212, v150 row_shr:4 row_mask:0xf bank_mask:0xa
	v_mov_b32_e32 v218, v77
	v_max3_f32 v61, v216, s59, v217
	v_mov_b32_e32 v215, v45
	v_max_f32_e32 v212, v212, v212
	v_max3_f32 v45, v61, v218, v215
	v_sub_f32_e32 v42, v214, v151
	v_sub_f32_e32 v74, v213, v151
	v_max_f32_e32 v150, v150, v212
	v_mov_b32_e32 v61, v45
	v_mov_b32_e32 v255, v45
	s_nop 1
	v_permlane16_swap_b32_e32 v61, v255
	v_mul_f32_e32 v42, 0x3fb8aa3b, v42
	v_mul_f32_e32 v90, 0x3fb8aa3b, v90
	v_mul_f32_e32 v74, 0x3fb8aa3b, v74
	v_mov_b32_dpp v214, v150 quad_perm:[2,3,0,1] row_mask:0xf bank_mask:0xf
	v_exp_f32_e32 v43, v43
	v_exp_f32_e32 v42, v42
	v_exp_f32_e32 v58, v58
	v_exp_f32_e32 v90, v90
	v_exp_f32_e32 v74, v74
	v_cvt_pk_bf16_f32 v148, v43, v59
	v_cvt_pk_bf16_f32 v149, v91, v75
	v_cvt_pk_bf16_f32 v212, v42, v58
	v_cvt_pk_bf16_f32 v213, v90, v74
	v_max_f32_e32 v214, v214, v214
	v_add_u32_e32 v77, 0x9c00, v186
	v_max_f32_e32 v61, v61, v255
	v_max_f32_e32 v150, v150, v214
	ds_write2_b64 v77, v[148:149], v[212:213] offset0:100 offset1:134
	s_nop 0
	v_mov_b32_dpp v214, v150 quad_perm:[1,0,3,2] row_mask:0xf bank_mask:0xf
	v_sub_f32_e32 v141, v141, v151
	v_mul_f32_e32 v141, 0x3fb8aa3b, v141
	v_exp_f32_e32 v133, v133
	s_waitcnt lgkmcnt(0)
	v_max3_f32 v150, v142, v150, v214
	v_max_f32_dpp v77, v61, v61 row_ror:8 row_mask:0xf bank_mask:0xf
	v_sub_f32_e32 v45, v92, v150
	s_nop 1
	v_mov_b32_dpp v92, v77 row_shl:4 row_mask:0xf bank_mask:0x5
	s_nop 1
	v_mov_b32_dpp v92, v77 row_shr:4 row_mask:0xf bank_mask:0xa
	v_sub_f32_e32 v60, v60, v150
	v_mul_f32_e32 v60, 0x3fb8aa3b, v60
	v_exp_f32_e32 v61, v60
	v_sub_f32_e32 v60, v76, v150
	v_max_f32_e32 v76, v92, v92
	v_max_f32_e32 v76, v77, v76
	s_nop 1
	v_mov_b32_dpp v92, v76 quad_perm:[2,3,0,1] row_mask:0xf bank_mask:0xf
	v_sub_f32_e32 v44, v44, v150
	v_mul_f32_e32 v44, 0x3fb8aa3b, v44
	v_exp_f32_e32 v77, v44
	v_mul_f32_e32 v60, 0x3fb8aa3b, v60
	v_max_f32_e32 v44, v92, v92
	v_max_f32_e32 v44, v76, v44
	v_exp_f32_e32 v93, v60
	s_nop 1
	v_mov_b32_dpp v60, v44 quad_perm:[1,0,3,2] row_mask:0xf bank_mask:0xf
	v_sub_f32_e32 v142, v142, v150
	v_mul_f32_e32 v76, 0x3fb8aa3b, v142
	v_exp_f32_e32 v142, v76
	v_mul_f32_e32 v45, 0x3fb8aa3b, v45
	v_max3_f32 v149, v143, v44, v60
	v_max3_f32 v60, v94, s59, v62
	v_max3_f32 v60, v60, v78, v46
	v_mov_b32_e32 v76, v60
	v_mov_b32_e32 v255, v60
	s_nop 1
	v_permlane16_swap_b32_e32 v76, v255
	v_sub_f32_e32 v92, v217, v149
	v_max_f32_e32 v76, v76, v255
	v_mov_b32_e32 v217, v95
	v_mul_f32_e32 v60, 0x3fb8aa3b, v92
	v_sub_f32_e32 v92, v218, v149
	v_max_f32_dpp v148, v76, v76 row_ror:8 row_mask:0xf bank_mask:0xf
	v_mov_b32_e32 v218, v63
	s_nop 0
	v_mov_b32_dpp v214, v148 row_shl:4 row_mask:0xf bank_mask:0x5
	s_nop 1
	v_mov_b32_dpp v214, v148 row_shr:4 row_mask:0xf bank_mask:0xa
	v_mov_b32_e32 v219, v79
	v_max3_f32 v63, v217, s59, v218
	v_mov_b32_e32 v96, v47
	v_max_f32_e32 v214, v214, v214
	v_max3_f32 v47, v63, v219, v96
	v_sub_f32_e32 v44, v216, v149
	v_sub_f32_e32 v76, v215, v149
	v_max_f32_e32 v148, v148, v214
	v_mov_b32_e32 v63, v47
	v_mov_b32_e32 v255, v47
	s_nop 1
	v_permlane16_swap_b32_e32 v63, v255
	v_mul_f32_e32 v44, 0x3fb8aa3b, v44
	v_mul_f32_e32 v92, 0x3fb8aa3b, v92
	v_mul_f32_e32 v76, 0x3fb8aa3b, v76
	v_mov_b32_dpp v216, v148 quad_perm:[2,3,0,1] row_mask:0xf bank_mask:0xf
	v_exp_f32_e32 v45, v45
	v_exp_f32_e32 v44, v44
	v_exp_f32_e32 v60, v60
	v_exp_f32_e32 v92, v92
	v_exp_f32_e32 v76, v76
	v_cvt_pk_bf16_f32 v212, v45, v61
	v_cvt_pk_bf16_f32 v213, v93, v77
	v_cvt_pk_bf16_f32 v214, v44, v60
	v_cvt_pk_bf16_f32 v215, v92, v76
	v_max_f32_e32 v216, v216, v216
	v_add_u32_e32 v79, 0xa000, v186
	v_max_f32_e32 v63, v63, v255
	v_max_f32_e32 v148, v148, v216
	ds_write2_b64 v79, v[212:213], v[214:215] offset0:176 offset1:210
	s_nop 0
	v_mov_b32_dpp v216, v148 quad_perm:[1,0,3,2] row_mask:0xf bank_mask:0xf
	v_sub_f32_e32 v143, v143, v149
	v_mul_f32_e32 v143, 0x3fb8aa3b, v143
	v_exp_f32_e32 v135, v135
	s_waitcnt lgkmcnt(0)
	v_max3_f32 v148, v144, v148, v216
	v_max_f32_dpp v79, v63, v63 row_ror:8 row_mask:0xf bank_mask:0xf
	v_sub_f32_e32 v47, v94, v148
	s_nop 1
	v_mov_b32_dpp v94, v79 row_shl:4 row_mask:0xf bank_mask:0x5
	s_nop 1
	v_mov_b32_dpp v94, v79 row_shr:4 row_mask:0xf bank_mask:0xa
	v_sub_f32_e32 v62, v62, v148
	v_mul_f32_e32 v62, 0x3fb8aa3b, v62
	v_exp_f32_e32 v63, v62
	v_sub_f32_e32 v62, v78, v148
	v_max_f32_e32 v78, v94, v94
	v_max_f32_e32 v78, v79, v78
	s_nop 1
	v_mov_b32_dpp v94, v78 quad_perm:[2,3,0,1] row_mask:0xf bank_mask:0xf
	v_sub_f32_e32 v46, v46, v148
	v_mul_f32_e32 v46, 0x3fb8aa3b, v46
	v_exp_f32_e32 v79, v46
	v_mul_f32_e32 v62, 0x3fb8aa3b, v62
	v_max_f32_e32 v46, v94, v94
	v_max_f32_e32 v46, v78, v46
	v_exp_f32_e32 v95, v62
	s_nop 1
	v_mov_b32_dpp v62, v46 quad_perm:[1,0,3,2] row_mask:0xf bank_mask:0xf
	v_sub_f32_e32 v144, v144, v148
	v_mul_f32_e32 v78, 0x3fb8aa3b, v144
	v_exp_f32_e32 v144, v78
	v_mul_f32_e32 v47, 0x3fb8aa3b, v47
	v_max3_f32 v147, v145, v46, v62
	v_sub_f32_e32 v78, v219, v147
	v_mul_f32_e32 v78, 0x3fb8aa3b, v78
	v_sub_f32_e32 v46, v217, v147
	v_sub_f32_e32 v62, v218, v147
	v_exp_f32_e32 v94, v78
	v_sub_f32_e32 v78, v96, v147
	v_sub_f32_e32 v145, v145, v147
	v_mul_f32_e32 v46, 0x3fb8aa3b, v46
	v_mul_f32_e32 v62, 0x3fb8aa3b, v62
	v_mul_f32_e32 v78, 0x3fb8aa3b, v78
	v_exp_f32_e32 v47, v47
	v_exp_f32_e32 v46, v46
	v_exp_f32_e32 v62, v62
	v_exp_f32_e32 v78, v78
	v_mul_f32_e32 v96, 0x3fb8aa3b, v145
	v_exp_f32_e32 v137, v137
	v_exp_f32_e32 v139, v139
	v_exp_f32_e32 v141, v141
	v_exp_f32_e32 v143, v143
	v_exp_f32_e32 v145, v96
	v_cvt_pk_bf16_f32 v208, v47, v63
	v_cvt_pk_bf16_f32 v209, v95, v79
	v_cvt_pk_bf16_f32 v210, v46, v62
	v_cvt_pk_bf16_f32 v211, v94, v78
	v_add_u32_e32 v96, 0xa400, v186
	ds_write2_b64 v96, v[208:209], v[210:211] offset0:116 offset1:150
	v_pk_mul_f32 v[14:15], v[14:15], v[144:145]
	v_pk_mul_f32 v[12:13], v[12:13], v[142:143]
	v_pk_mul_f32 v[10:11], v[10:11], v[140:141]
	v_pk_mul_f32 v[8:9], v[8:9], v[138:139]
	v_pk_mul_f32 v[6:7], v[6:7], v[136:137]
	v_pk_mul_f32 v[4:5], v[4:5], v[134:135]
	v_pk_mul_f32 v[2:3], v[2:3], v[132:133]
	v_pk_mul_f32 v[0:1], v[0:1], v[130:131]
	v_pk_mul_f32 v[30:31], v[30:31], v[144:145]
	v_pk_mul_f32 v[28:29], v[28:29], v[142:143]
	v_pk_mul_f32 v[26:27], v[26:27], v[140:141]
	v_pk_mul_f32 v[24:25], v[24:25], v[138:139]
	v_pk_mul_f32 v[22:23], v[22:23], v[136:137]
	v_pk_mul_f32 v[20:21], v[20:21], v[134:135]
	v_pk_mul_f32 v[18:19], v[18:19], v[132:133]
	v_pk_mul_f32 v[16:17], v[16:17], v[130:131]
	s_mov_b32 s2, -16
	v_mov_b32_e32 v96, v185
	v_mov_b32_e32 v208, v184
	s_branch .Latt_join
.LBB0_722:
	v_mbcnt_hi_u32_b32 v35, -1, v195
	v_and_b32_e32 v32, 64, v35
	v_add_u32_e32 v36, 64, v32
	v_xor_b32_e32 v37, 16, v35
	v_cmp_lt_i32_e32 vcc, v37, v36
	v_xor_b32_e32 v38, 8, v35
	s_lshl_b32 s0, s42, 1
	v_cndmask_b32_e32 v37, v35, v37, vcc
	v_lshlrev_b32_e32 v39, 2, v37
	v_mov_b32_e32 v37, v129
	v_mov_b32_e32 v255, v129
	s_nop 1
	v_permlane16_swap_b32_e32 v37, v255
	v_cmp_lt_i32_e32 vcc, v38, v36
	v_readlane_b32 s1, v249, 25
	s_add_u32 s0, s1, s0
	v_cndmask_b32_e32 v38, v35, v38, vcc
	s_waitcnt lgkmcnt(0)
	v_add_f32_e32 v37, v37, v255
	v_lshlrev_b32_e32 v40, 2, v38
	v_readlane_b32 s1, v249, 26
	s_addc_u32 s1, s1, 0
	v_lshlrev_b32_e32 v96, 1, v157
	v_lshl_add_u64 v[32:33], s[0:1], 0, v[96:97]
	v_add_f32_dpp v37, v37, v37 row_ror:8 row_mask:0xf bank_mask:0xf
	v_xor_b32_e32 v38, 4, v35
	v_cmp_lt_i32_e32 vcc, v38, v36
	v_add_u32_e32 v34, s4, v159
	s_nop 0
	v_cndmask_b32_e32 v38, v35, v38, vcc
	v_lshlrev_b32_e32 v38, 2, v38
	v_mov_b32_dpp v41, v37 row_shl:4 row_mask:0xf bank_mask:0x5
	v_mov_b32_dpp v41, v37 row_shr:4 row_mask:0xf bank_mask:0xa
	v_add_f32_e32 v41, v37, v41
	v_xor_b32_e32 v37, 2, v35
	v_cmp_lt_i32_e32 vcc, v37, v36
	s_nop 1
	v_cndmask_b32_e32 v37, v35, v37, vcc
	v_lshlrev_b32_e32 v37, 2, v37
	v_add_f32_dpp v41, v41, v41 quad_perm:[2,3,0,1] row_mask:0xf bank_mask:0xf
	v_xor_b32_e32 v42, 1, v35
	v_cmp_lt_i32_e32 vcc, v42, v36
	s_nop 1
	v_cndmask_b32_e32 v35, v35, v42, vcc
	v_lshlrev_b32_e32 v36, 2, v35
	s_nop 0
	v_add_f32_dpp v35, v41, v41 quad_perm:[1,0,3,2] row_mask:0xf bank_mask:0xf
	v_sub_f32_e32 v41, v146, v207
	v_mul_f32_e32 v41, 0x3fb8aa3b, v41
	v_exp_f32_e32 v41, v41
	s_nop 0
	v_add_f32_e32 v35, v41, v35
	v_div_scale_f32 v41, s[0:1], v35, v35, 1.0
	v_rcp_f32_e32 v42, v41
	s_nop 0
	v_fma_f32 v43, -v41, v42, 1.0
	v_fmac_f32_e32 v42, v43, v42
	v_div_scale_f32 v43, vcc, 1.0, v35, 1.0
	v_mul_f32_e32 v44, v43, v42
	v_fma_f32 v45, -v41, v44, v43
	v_fmac_f32_e32 v44, v45, v42
	v_fma_f32 v41, -v41, v44, v43
	v_div_fmas_f32 v41, v41, v42, v44
	v_div_fixup_f32 v41, v41, v35, 1.0
	v_ashrrev_i32_e32 v35, 31, v34
	v_mul_f32_e32 v0, v0, v41
	v_lshlrev_b64 v[42:43], 10, v[34:35]
	v_cvt_pk_bf16_f32 v0, v0, s0
	v_lshl_add_u64 v[42:43], v[32:33], 0, v[42:43]
	global_store_short v[42:43], v0, off
	v_mul_f32_e32 v0, v16, v41
	v_cvt_pk_bf16_f32 v0, v0, s0
	global_store_short v[42:43], v0, off offset:64
	v_mov_b32_e32 v0, v128
	v_mov_b32_e32 v255, v128
	s_nop 1
	v_permlane16_swap_b32_e32 v0, v255
	s_nop 1
	v_add_f32_e32 v0, v0, v255
	s_nop 1
	v_mov_b32_dpp v16, v0 row_ror:8 row_mask:0xf bank_mask:0xf
	s_nop 0
	v_add_f32_e32 v0, v0, v16
	s_nop 1
	v_mov_b32_dpp v16, v0 row_shl:4 row_mask:0xf bank_mask:0x5
	v_mov_b32_dpp v16, v0 row_shr:4 row_mask:0xf bank_mask:0xa
	s_nop 0
	v_add_f32_e32 v0, v0, v16
	s_nop 1
	v_mov_b32_dpp v16, v0 quad_perm:[2,3,0,1] row_mask:0xf bank_mask:0xf
	v_add_f32_e32 v0, v0, v16
	s_nop 1
	v_add_f32_dpp v0, v0, v0 quad_perm:[1,0,3,2] row_mask:0xf bank_mask:0xf
	v_sub_f32_e32 v16, v146, v206
	v_mul_f32_e32 v16, 0x3fb8aa3b, v16
	v_exp_f32_e32 v16, v16
	s_nop 0
	v_add_f32_e32 v0, v16, v0
	v_div_scale_f32 v16, s[0:1], v0, v0, 1.0
	v_rcp_f32_e32 v35, v16
	s_nop 0
	v_fma_f32 v41, -v16, v35, 1.0
	v_fmac_f32_e32 v35, v41, v35
	v_div_scale_f32 v41, vcc, 1.0, v0, 1.0
	v_mul_f32_e32 v42, v41, v35
	v_fma_f32 v43, -v16, v42, v41
	v_fmac_f32_e32 v42, v43, v35
	v_fma_f32 v16, -v16, v42, v41
	v_div_fmas_f32 v16, v16, v35, v42
	v_div_fixup_f32 v16, v16, v0, 1.0
	v_add_u32_e32 v0, 1, v34
	v_mul_f32_e32 v1, v1, v16
	v_cvt_pk_bf16_f32 v35, v1, s0
	v_ashrrev_i32_e32 v1, 31, v0
	v_lshlrev_b64 v[0:1], 10, v[0:1]
	v_mul_f32_e32 v16, v17, v16
	v_lshl_add_u64 v[0:1], v[32:33], 0, v[0:1]
	v_cvt_pk_bf16_f32 v16, v16, s0
	global_store_short v[0:1], v35, off
	global_store_short v[0:1], v16, off offset:64
	v_mov_b32_e32 v0, v127
	v_mov_b32_e32 v255, v127
	s_nop 1
	v_permlane16_swap_b32_e32 v0, v255
	s_nop 1
	v_add_f32_e32 v0, v0, v255
	s_nop 1
	v_mov_b32_dpp v1, v0 row_ror:8 row_mask:0xf bank_mask:0xf
	s_nop 0
	v_add_f32_e32 v0, v0, v1
	s_nop 1
	v_mov_b32_dpp v1, v0 row_shl:4 row_mask:0xf bank_mask:0x5
	v_mov_b32_dpp v1, v0 row_shr:4 row_mask:0xf bank_mask:0xa
	s_nop 0
	v_add_f32_e32 v0, v0, v1
	s_nop 1
	v_mov_b32_dpp v1, v0 quad_perm:[2,3,0,1] row_mask:0xf bank_mask:0xf
	v_add_f32_e32 v0, v0, v1
	s_nop 1
	v_add_f32_dpp v0, v0, v0 quad_perm:[1,0,3,2] row_mask:0xf bank_mask:0xf
	v_sub_f32_e32 v1, v146, v189
	v_mul_f32_e32 v1, 0x3fb8aa3b, v1
	v_exp_f32_e32 v1, v1
	s_nop 0
	v_add_f32_e32 v0, v1, v0
	v_div_scale_f32 v1, s[0:1], v0, v0, 1.0
	v_rcp_f32_e32 v16, v1
	s_nop 0
	v_fma_f32 v17, -v1, v16, 1.0
	v_fmac_f32_e32 v16, v17, v16
	v_div_scale_f32 v17, vcc, 1.0, v0, 1.0
	v_mul_f32_e32 v35, v17, v16
	v_fma_f32 v41, -v1, v35, v17
	v_fmac_f32_e32 v35, v41, v16
	v_fma_f32 v1, -v1, v35, v17
	v_div_fmas_f32 v1, v1, v16, v35
	v_div_fixup_f32 v16, v1, v0, 1.0
	v_add_u32_e32 v0, 2, v34
	v_mul_f32_e32 v1, v2, v16
	v_cvt_pk_bf16_f32 v2, v1, s0
	v_ashrrev_i32_e32 v1, 31, v0
	v_lshlrev_b64 v[0:1], 10, v[0:1]
	v_lshl_add_u64 v[0:1], v[32:33], 0, v[0:1]
	global_store_short v[0:1], v2, off
	v_mul_f32_e32 v2, v18, v16
	v_cvt_pk_bf16_f32 v2, v2, s0
	global_store_short v[0:1], v2, off offset:64
	v_mov_b32_e32 v0, v126
	v_mov_b32_e32 v255, v126
	s_nop 1
	v_permlane16_swap_b32_e32 v0, v255
	s_nop 1
	v_add_f32_e32 v0, v0, v255
	s_nop 1
	v_mov_b32_dpp v1, v0 row_ror:8 row_mask:0xf bank_mask:0xf
	s_nop 0
	v_add_f32_e32 v0, v0, v1
	s_nop 1
	v_mov_b32_dpp v1, v0 row_shl:4 row_mask:0xf bank_mask:0x5
	v_mov_b32_dpp v1, v0 row_shr:4 row_mask:0xf bank_mask:0xa
	s_nop 0
	v_add_f32_e32 v0, v0, v1
	s_nop 1
	v_mov_b32_dpp v1, v0 quad_perm:[2,3,0,1] row_mask:0xf bank_mask:0xf
	v_add_f32_e32 v0, v0, v1
	s_nop 1
	v_add_f32_dpp v0, v0, v0 quad_perm:[1,0,3,2] row_mask:0xf bank_mask:0xf
	v_sub_f32_e32 v1, v146, v188
	v_mul_f32_e32 v1, 0x3fb8aa3b, v1
	v_exp_f32_e32 v1, v1
	s_nop 0
	v_add_f32_e32 v0, v1, v0
	v_div_scale_f32 v1, s[0:1], v0, v0, 1.0
	v_rcp_f32_e32 v2, v1
	s_nop 0
	v_fma_f32 v16, -v1, v2, 1.0
	v_fmac_f32_e32 v2, v16, v2
	v_div_scale_f32 v16, vcc, 1.0, v0, 1.0
	v_mul_f32_e32 v17, v16, v2
	v_fma_f32 v18, -v1, v17, v16
	v_fmac_f32_e32 v17, v18, v2
	v_fma_f32 v1, -v1, v17, v16
	v_div_fmas_f32 v1, v1, v2, v17
	v_div_fixup_f32 v2, v1, v0, 1.0
	v_add_u32_e32 v0, 3, v34
	v_mul_f32_e32 v1, v3, v2
	v_cvt_pk_bf16_f32 v3, v1, s0
	v_ashrrev_i32_e32 v1, 31, v0
	v_lshlrev_b64 v[0:1], 10, v[0:1]
	v_mul_f32_e32 v2, v19, v2
	v_lshl_add_u64 v[0:1], v[32:33], 0, v[0:1]
	v_cvt_pk_bf16_f32 v2, v2, s0
	global_store_short v[0:1], v3, off
	global_store_short v[0:1], v2, off offset:64
	v_mov_b32_e32 v0, v125
	v_mov_b32_e32 v255, v125
	s_nop 1
	v_permlane16_swap_b32_e32 v0, v255
	s_nop 1
	v_add_f32_e32 v0, v0, v255
	s_nop 1
	v_mov_b32_dpp v1, v0 row_ror:8 row_mask:0xf bank_mask:0xf
	s_nop 0
	v_add_f32_e32 v0, v0, v1
	s_nop 1
	v_mov_b32_dpp v1, v0 row_shl:4 row_mask:0xf bank_mask:0x5
	v_mov_b32_dpp v1, v0 row_shr:4 row_mask:0xf bank_mask:0xa
	s_nop 0
	v_add_f32_e32 v0, v0, v1
	s_nop 1
	v_mov_b32_dpp v1, v0 quad_perm:[2,3,0,1] row_mask:0xf bank_mask:0xf
	v_add_f32_e32 v0, v0, v1
	s_nop 1
	v_add_f32_dpp v0, v0, v0 quad_perm:[1,0,3,2] row_mask:0xf bank_mask:0xf
	v_sub_f32_e32 v1, v146, v187
	v_mul_f32_e32 v1, 0x3fb8aa3b, v1
	v_exp_f32_e32 v1, v1
	s_nop 0
	v_add_f32_e32 v0, v1, v0
	v_div_scale_f32 v1, s[0:1], v0, v0, 1.0
	v_rcp_f32_e32 v2, v1
	s_nop 0
	v_fma_f32 v3, -v1, v2, 1.0
	v_fmac_f32_e32 v2, v3, v2
	v_div_scale_f32 v3, vcc, 1.0, v0, 1.0
	v_mul_f32_e32 v16, v3, v2
	v_fma_f32 v17, -v1, v16, v3
	v_fmac_f32_e32 v16, v17, v2
	v_fma_f32 v1, -v1, v16, v3
	v_div_fmas_f32 v1, v1, v2, v16
	v_div_fixup_f32 v2, v1, v0, 1.0
	v_add_u32_e32 v0, 8, v34
	v_mul_f32_e32 v1, v4, v2
	v_cvt_pk_bf16_f32 v3, v1, s0
	v_ashrrev_i32_e32 v1, 31, v0
	v_lshlrev_b64 v[0:1], 10, v[0:1]
	v_mul_f32_e32 v2, v20, v2
	v_lshl_add_u64 v[0:1], v[32:33], 0, v[0:1]
	v_cvt_pk_bf16_f32 v2, v2, s0
	global_store_short v[0:1], v3, off
	global_store_short v[0:1], v2, off offset:64
	v_mov_b32_e32 v0, v124
	v_mov_b32_e32 v255, v124
	s_nop 1
	v_permlane16_swap_b32_e32 v0, v255
	s_nop 1
	v_add_f32_e32 v0, v0, v255
	s_nop 1
	v_mov_b32_dpp v1, v0 row_ror:8 row_mask:0xf bank_mask:0xf
	s_nop 0
	v_add_f32_e32 v0, v0, v1
	s_nop 1
	v_mov_b32_dpp v1, v0 row_shl:4 row_mask:0xf bank_mask:0x5
	v_mov_b32_dpp v1, v0 row_shr:4 row_mask:0xf bank_mask:0xa
	s_nop 0
	v_add_f32_e32 v0, v0, v1
	s_nop 1
	v_mov_b32_dpp v1, v0 quad_perm:[2,3,0,1] row_mask:0xf bank_mask:0xf
	v_add_f32_e32 v0, v0, v1
	s_nop 1
	v_add_f32_dpp v0, v0, v0 quad_perm:[1,0,3,2] row_mask:0xf bank_mask:0xf
	v_sub_f32_e32 v1, v146, v160
	v_mul_f32_e32 v1, 0x3fb8aa3b, v1
	v_exp_f32_e32 v1, v1
	s_nop 0
	v_add_f32_e32 v0, v1, v0
	v_div_scale_f32 v1, s[0:1], v0, v0, 1.0
	v_rcp_f32_e32 v2, v1
	s_nop 0
	v_fma_f32 v3, -v1, v2, 1.0
	v_fmac_f32_e32 v2, v3, v2
	v_div_scale_f32 v3, vcc, 1.0, v0, 1.0
	v_mul_f32_e32 v4, v3, v2
	v_fma_f32 v16, -v1, v4, v3
	v_fmac_f32_e32 v4, v16, v2
	v_fma_f32 v1, -v1, v4, v3
	v_div_fmas_f32 v1, v1, v2, v4
	v_div_fixup_f32 v2, v1, v0, 1.0
	v_add_u32_e32 v0, 9, v34
	v_mul_f32_e32 v1, v5, v2
	v_cvt_pk_bf16_f32 v3, v1, s0
	v_ashrrev_i32_e32 v1, 31, v0
	v_lshlrev_b64 v[0:1], 10, v[0:1]
	v_mul_f32_e32 v2, v21, v2
	v_lshl_add_u64 v[0:1], v[32:33], 0, v[0:1]
	v_cvt_pk_bf16_f32 v2, v2, s0
	global_store_short v[0:1], v3, off
	global_store_short v[0:1], v2, off offset:64
	v_mov_b32_e32 v0, v123
	v_mov_b32_e32 v255, v123
	s_nop 1
	v_permlane16_swap_b32_e32 v0, v255
	s_nop 1
	v_add_f32_e32 v0, v0, v255
	s_nop 1
	v_mov_b32_dpp v1, v0 row_ror:8 row_mask:0xf bank_mask:0xf
	s_nop 0
	v_add_f32_e32 v0, v0, v1
	s_nop 1
	v_mov_b32_dpp v1, v0 row_shl:4 row_mask:0xf bank_mask:0x5
	v_mov_b32_dpp v1, v0 row_shr:4 row_mask:0xf bank_mask:0xa
	s_nop 0
	v_add_f32_e32 v0, v0, v1
	s_nop 1
	v_mov_b32_dpp v1, v0 quad_perm:[2,3,0,1] row_mask:0xf bank_mask:0xf
	v_add_f32_e32 v0, v0, v1
	s_nop 1
	v_add_f32_dpp v0, v0, v0 quad_perm:[1,0,3,2] row_mask:0xf bank_mask:0xf
	v_sub_f32_e32 v1, v146, v156
	v_mul_f32_e32 v1, 0x3fb8aa3b, v1
	v_exp_f32_e32 v1, v1
	s_nop 0
	v_add_f32_e32 v0, v1, v0
	v_div_scale_f32 v1, s[0:1], v0, v0, 1.0
	v_rcp_f32_e32 v2, v1
	s_nop 0
	v_fma_f32 v3, -v1, v2, 1.0
	v_fmac_f32_e32 v2, v3, v2
	v_div_scale_f32 v3, vcc, 1.0, v0, 1.0
	v_mul_f32_e32 v4, v3, v2
	v_fma_f32 v5, -v1, v4, v3
	v_fmac_f32_e32 v4, v5, v2
	v_fma_f32 v1, -v1, v4, v3
	v_div_fmas_f32 v1, v1, v2, v4
	v_div_fixup_f32 v2, v1, v0, 1.0
	v_add_u32_e32 v0, 10, v34
	v_mul_f32_e32 v1, v6, v2
	v_cvt_pk_bf16_f32 v3, v1, s0
	v_ashrrev_i32_e32 v1, 31, v0
	v_lshlrev_b64 v[0:1], 10, v[0:1]
	v_mul_f32_e32 v2, v22, v2
	v_lshl_add_u64 v[0:1], v[32:33], 0, v[0:1]
	v_cvt_pk_bf16_f32 v2, v2, s0
	global_store_short v[0:1], v3, off
	global_store_short v[0:1], v2, off offset:64
	v_mov_b32_e32 v0, v122
	v_mov_b32_e32 v255, v122
	s_nop 1
	v_permlane16_swap_b32_e32 v0, v255
	s_nop 1
	v_add_f32_e32 v0, v0, v255
	s_nop 1
	v_mov_b32_dpp v1, v0 row_ror:8 row_mask:0xf bank_mask:0xf
	s_nop 0
	v_add_f32_e32 v0, v0, v1
	s_nop 1
	v_mov_b32_dpp v1, v0 row_shl:4 row_mask:0xf bank_mask:0x5
	v_mov_b32_dpp v1, v0 row_shr:4 row_mask:0xf bank_mask:0xa
	s_nop 0
	v_add_f32_e32 v0, v0, v1
	s_nop 1
	v_mov_b32_dpp v1, v0 quad_perm:[2,3,0,1] row_mask:0xf bank_mask:0xf
	v_add_f32_e32 v0, v0, v1
	s_nop 1
	v_add_f32_dpp v0, v0, v0 quad_perm:[1,0,3,2] row_mask:0xf bank_mask:0xf
	v_sub_f32_e32 v1, v146, v155
	v_mul_f32_e32 v1, 0x3fb8aa3b, v1
	v_exp_f32_e32 v1, v1
	s_nop 0
	v_add_f32_e32 v0, v1, v0
	v_div_scale_f32 v1, s[0:1], v0, v0, 1.0
	v_rcp_f32_e32 v2, v1
	s_nop 0
	v_fma_f32 v3, -v1, v2, 1.0
	v_fmac_f32_e32 v2, v3, v2
	v_div_scale_f32 v3, vcc, 1.0, v0, 1.0
	v_mul_f32_e32 v4, v3, v2
	v_fma_f32 v5, -v1, v4, v3
	v_fmac_f32_e32 v4, v5, v2
	v_fma_f32 v1, -v1, v4, v3
	v_div_fmas_f32 v1, v1, v2, v4
	v_div_fixup_f32 v2, v1, v0, 1.0
	v_add_u32_e32 v0, 11, v34
	v_mul_f32_e32 v1, v7, v2
	v_cvt_pk_bf16_f32 v3, v1, s0
	v_ashrrev_i32_e32 v1, 31, v0
	v_lshlrev_b64 v[0:1], 10, v[0:1]
	v_mul_f32_e32 v2, v23, v2
	v_lshl_add_u64 v[0:1], v[32:33], 0, v[0:1]
	v_cvt_pk_bf16_f32 v2, v2, s0
	global_store_short v[0:1], v3, off
	global_store_short v[0:1], v2, off offset:64
	v_mov_b32_e32 v0, v121
	v_mov_b32_e32 v255, v121
	s_nop 1
	v_permlane16_swap_b32_e32 v0, v255
	s_nop 1
	v_add_f32_e32 v0, v0, v255
	s_nop 1
	v_mov_b32_dpp v1, v0 row_ror:8 row_mask:0xf bank_mask:0xf
	s_nop 0
	v_add_f32_e32 v0, v0, v1
	s_nop 1
	v_mov_b32_dpp v1, v0 row_shl:4 row_mask:0xf bank_mask:0x5
	v_mov_b32_dpp v1, v0 row_shr:4 row_mask:0xf bank_mask:0xa
	s_nop 0
	v_add_f32_e32 v0, v0, v1
	s_nop 1
	v_mov_b32_dpp v1, v0 quad_perm:[2,3,0,1] row_mask:0xf bank_mask:0xf
	v_add_f32_e32 v0, v0, v1
	s_nop 1
	v_add_f32_dpp v0, v0, v0 quad_perm:[1,0,3,2] row_mask:0xf bank_mask:0xf
	v_sub_f32_e32 v1, v146, v154
	v_mul_f32_e32 v1, 0x3fb8aa3b, v1
	v_exp_f32_e32 v1, v1
	s_nop 0
	v_add_f32_e32 v0, v1, v0
	v_div_scale_f32 v1, s[0:1], v0, v0, 1.0
	v_rcp_f32_e32 v2, v1
	s_nop 0
	v_fma_f32 v3, -v1, v2, 1.0
	v_fmac_f32_e32 v2, v3, v2
	v_div_scale_f32 v3, vcc, 1.0, v0, 1.0
	v_mul_f32_e32 v4, v3, v2
	v_fma_f32 v5, -v1, v4, v3
	v_fmac_f32_e32 v4, v5, v2
	v_fma_f32 v1, -v1, v4, v3
	v_div_fmas_f32 v1, v1, v2, v4
	v_div_fixup_f32 v2, v1, v0, 1.0
	v_add_u32_e32 v0, 16, v34
	v_mul_f32_e32 v1, v8, v2
	v_cvt_pk_bf16_f32 v3, v1, s0
	v_ashrrev_i32_e32 v1, 31, v0
	v_lshlrev_b64 v[0:1], 10, v[0:1]
	v_mul_f32_e32 v2, v24, v2
	v_lshl_add_u64 v[0:1], v[32:33], 0, v[0:1]
	v_cvt_pk_bf16_f32 v2, v2, s0
	global_store_short v[0:1], v3, off
	global_store_short v[0:1], v2, off offset:64
	v_mov_b32_e32 v0, v120
	v_mov_b32_e32 v255, v120
	s_nop 1
	v_permlane16_swap_b32_e32 v0, v255
	s_nop 1
	v_add_f32_e32 v0, v0, v255
	s_nop 1
	v_mov_b32_dpp v1, v0 row_ror:8 row_mask:0xf bank_mask:0xf
	s_nop 0
	v_add_f32_e32 v0, v0, v1
	s_nop 1
	v_mov_b32_dpp v1, v0 row_shl:4 row_mask:0xf bank_mask:0x5
	v_mov_b32_dpp v1, v0 row_shr:4 row_mask:0xf bank_mask:0xa
	s_nop 0
	v_add_f32_e32 v0, v0, v1
	s_nop 1
	v_mov_b32_dpp v1, v0 quad_perm:[2,3,0,1] row_mask:0xf bank_mask:0xf
	v_add_f32_e32 v0, v0, v1
	s_nop 1
	v_add_f32_dpp v0, v0, v0 quad_perm:[1,0,3,2] row_mask:0xf bank_mask:0xf
	v_sub_f32_e32 v1, v146, v153
	v_mul_f32_e32 v1, 0x3fb8aa3b, v1
	v_exp_f32_e32 v1, v1
	s_nop 0
	v_add_f32_e32 v0, v1, v0
	v_div_scale_f32 v1, s[0:1], v0, v0, 1.0
	v_rcp_f32_e32 v2, v1
	s_nop 0
	v_fma_f32 v3, -v1, v2, 1.0
	v_fmac_f32_e32 v2, v3, v2
	v_div_scale_f32 v3, vcc, 1.0, v0, 1.0
	v_mul_f32_e32 v4, v3, v2
	v_fma_f32 v5, -v1, v4, v3
	v_fmac_f32_e32 v4, v5, v2
	v_fma_f32 v1, -v1, v4, v3
	v_div_fmas_f32 v1, v1, v2, v4
	v_div_fixup_f32 v2, v1, v0, 1.0
	v_add_u32_e32 v0, 17, v34
	v_mul_f32_e32 v1, v9, v2
	v_cvt_pk_bf16_f32 v3, v1, s0
	v_ashrrev_i32_e32 v1, 31, v0
	v_lshlrev_b64 v[0:1], 10, v[0:1]
	v_mul_f32_e32 v2, v25, v2
	v_lshl_add_u64 v[0:1], v[32:33], 0, v[0:1]
	v_cvt_pk_bf16_f32 v2, v2, s0
	global_store_short v[0:1], v3, off
	global_store_short v[0:1], v2, off offset:64
	v_mov_b32_e32 v0, v119
	v_mov_b32_e32 v255, v119
	s_nop 1
	v_permlane16_swap_b32_e32 v0, v255
	s_nop 1
	v_add_f32_e32 v0, v0, v255
	s_nop 1
	v_mov_b32_dpp v1, v0 row_ror:8 row_mask:0xf bank_mask:0xf
	s_nop 0
	v_add_f32_e32 v0, v0, v1
	s_nop 1
	v_mov_b32_dpp v1, v0 row_shl:4 row_mask:0xf bank_mask:0x5
	v_mov_b32_dpp v1, v0 row_shr:4 row_mask:0xf bank_mask:0xa
	s_nop 0
	v_add_f32_e32 v0, v0, v1
	s_nop 1
	v_mov_b32_dpp v1, v0 quad_perm:[2,3,0,1] row_mask:0xf bank_mask:0xf
	v_add_f32_e32 v0, v0, v1
	s_nop 1
	v_add_f32_dpp v0, v0, v0 quad_perm:[1,0,3,2] row_mask:0xf bank_mask:0xf
	v_sub_f32_e32 v1, v146, v152
	v_mul_f32_e32 v1, 0x3fb8aa3b, v1
	v_exp_f32_e32 v1, v1
	s_nop 0
	v_add_f32_e32 v0, v1, v0
	v_div_scale_f32 v1, s[0:1], v0, v0, 1.0
	v_rcp_f32_e32 v2, v1
	s_nop 0
	v_fma_f32 v3, -v1, v2, 1.0
	v_fmac_f32_e32 v2, v3, v2
	v_div_scale_f32 v3, vcc, 1.0, v0, 1.0
	v_mul_f32_e32 v4, v3, v2
	v_fma_f32 v5, -v1, v4, v3
	v_fmac_f32_e32 v4, v5, v2
	v_fma_f32 v1, -v1, v4, v3
	v_div_fmas_f32 v1, v1, v2, v4
	v_div_fixup_f32 v2, v1, v0, 1.0
	v_add_u32_e32 v0, 18, v34
	v_mul_f32_e32 v1, v10, v2
	v_cvt_pk_bf16_f32 v3, v1, s0
	v_ashrrev_i32_e32 v1, 31, v0
	v_lshlrev_b64 v[0:1], 10, v[0:1]
	v_mul_f32_e32 v2, v26, v2
	v_lshl_add_u64 v[0:1], v[32:33], 0, v[0:1]
	v_cvt_pk_bf16_f32 v2, v2, s0
	global_store_short v[0:1], v3, off
	global_store_short v[0:1], v2, off offset:64
	v_mov_b32_e32 v0, v118
	v_mov_b32_e32 v255, v118
	s_nop 1
	v_permlane16_swap_b32_e32 v0, v255
	s_nop 1
	v_add_f32_e32 v0, v0, v255
	s_nop 1
	v_mov_b32_dpp v1, v0 row_ror:8 row_mask:0xf bank_mask:0xf
	s_nop 0
	v_add_f32_e32 v0, v0, v1
	s_nop 1
	v_mov_b32_dpp v1, v0 row_shl:4 row_mask:0xf bank_mask:0x5
	v_mov_b32_dpp v1, v0 row_shr:4 row_mask:0xf bank_mask:0xa
	s_nop 0
	v_add_f32_e32 v0, v0, v1
	s_nop 1
	v_mov_b32_dpp v1, v0 quad_perm:[2,3,0,1] row_mask:0xf bank_mask:0xf
	v_add_f32_e32 v0, v0, v1
	s_nop 1
	v_add_f32_dpp v0, v0, v0 quad_perm:[1,0,3,2] row_mask:0xf bank_mask:0xf
	v_sub_f32_e32 v1, v146, v151
	v_mul_f32_e32 v1, 0x3fb8aa3b, v1
	v_exp_f32_e32 v1, v1
	s_nop 0
	v_add_f32_e32 v0, v1, v0
	v_div_scale_f32 v1, s[0:1], v0, v0, 1.0
	v_rcp_f32_e32 v2, v1
	s_nop 0
	v_fma_f32 v3, -v1, v2, 1.0
	v_fmac_f32_e32 v2, v3, v2
	v_div_scale_f32 v3, vcc, 1.0, v0, 1.0
	v_mul_f32_e32 v4, v3, v2
	v_fma_f32 v5, -v1, v4, v3
	v_fmac_f32_e32 v4, v5, v2
	v_fma_f32 v1, -v1, v4, v3
	v_div_fmas_f32 v1, v1, v2, v4
	v_div_fixup_f32 v2, v1, v0, 1.0
	v_add_u32_e32 v0, 19, v34
	v_mul_f32_e32 v1, v11, v2
	v_cvt_pk_bf16_f32 v3, v1, s0
	v_ashrrev_i32_e32 v1, 31, v0
	v_lshlrev_b64 v[0:1], 10, v[0:1]
	v_mul_f32_e32 v2, v27, v2
	v_lshl_add_u64 v[0:1], v[32:33], 0, v[0:1]
	v_cvt_pk_bf16_f32 v2, v2, s0
	global_store_short v[0:1], v3, off
	global_store_short v[0:1], v2, off offset:64
	v_mov_b32_e32 v0, v117
	v_mov_b32_e32 v255, v117
	s_nop 1
	v_permlane16_swap_b32_e32 v0, v255
	s_nop 1
	v_add_f32_e32 v0, v0, v255
	s_nop 1
	v_mov_b32_dpp v1, v0 row_ror:8 row_mask:0xf bank_mask:0xf
	s_nop 0
	v_add_f32_e32 v0, v0, v1
	s_nop 1
	v_mov_b32_dpp v1, v0 row_shl:4 row_mask:0xf bank_mask:0x5
	v_mov_b32_dpp v1, v0 row_shr:4 row_mask:0xf bank_mask:0xa
	s_nop 0
	v_add_f32_e32 v0, v0, v1
	s_nop 1
	v_mov_b32_dpp v1, v0 quad_perm:[2,3,0,1] row_mask:0xf bank_mask:0xf
	v_add_f32_e32 v0, v0, v1
	s_nop 1
	v_add_f32_dpp v0, v0, v0 quad_perm:[1,0,3,2] row_mask:0xf bank_mask:0xf
	v_sub_f32_e32 v1, v146, v150
	v_mul_f32_e32 v1, 0x3fb8aa3b, v1
	v_exp_f32_e32 v1, v1
	s_nop 0
	v_add_f32_e32 v0, v1, v0
	v_div_scale_f32 v1, s[0:1], v0, v0, 1.0
	v_rcp_f32_e32 v2, v1
	s_nop 0
	v_fma_f32 v3, -v1, v2, 1.0
	v_fmac_f32_e32 v2, v3, v2
	v_div_scale_f32 v3, vcc, 1.0, v0, 1.0
	v_mul_f32_e32 v4, v3, v2
	v_fma_f32 v5, -v1, v4, v3
	v_fmac_f32_e32 v4, v5, v2
	v_fma_f32 v1, -v1, v4, v3
	v_div_fmas_f32 v1, v1, v2, v4
	v_div_fixup_f32 v2, v1, v0, 1.0
	v_add_u32_e32 v0, 24, v34
	v_mul_f32_e32 v1, v12, v2
	v_cvt_pk_bf16_f32 v3, v1, s0
	v_ashrrev_i32_e32 v1, 31, v0
	v_lshlrev_b64 v[0:1], 10, v[0:1]
	v_mul_f32_e32 v2, v28, v2
	v_lshl_add_u64 v[0:1], v[32:33], 0, v[0:1]
	v_cvt_pk_bf16_f32 v2, v2, s0
	global_store_short v[0:1], v3, off
	global_store_short v[0:1], v2, off offset:64
	v_mov_b32_e32 v0, v116
	v_mov_b32_e32 v255, v116
	s_nop 1
	v_permlane16_swap_b32_e32 v0, v255
	s_nop 1
	v_add_f32_e32 v0, v0, v255
	s_nop 1
	v_mov_b32_dpp v1, v0 row_ror:8 row_mask:0xf bank_mask:0xf
	s_nop 0
	v_add_f32_e32 v0, v0, v1
	s_nop 1
	v_mov_b32_dpp v1, v0 row_shl:4 row_mask:0xf bank_mask:0x5
	v_mov_b32_dpp v1, v0 row_shr:4 row_mask:0xf bank_mask:0xa
	s_nop 0
	v_add_f32_e32 v0, v0, v1
	s_nop 1
	v_mov_b32_dpp v1, v0 quad_perm:[2,3,0,1] row_mask:0xf bank_mask:0xf
	v_add_f32_e32 v0, v0, v1
	s_nop 1
	v_add_f32_dpp v0, v0, v0 quad_perm:[1,0,3,2] row_mask:0xf bank_mask:0xf
	v_sub_f32_e32 v1, v146, v149
	v_mul_f32_e32 v1, 0x3fb8aa3b, v1
	v_exp_f32_e32 v1, v1
	s_nop 0
	v_add_f32_e32 v0, v1, v0
	v_div_scale_f32 v1, s[0:1], v0, v0, 1.0
	v_rcp_f32_e32 v2, v1
	s_nop 0
	v_fma_f32 v3, -v1, v2, 1.0
	v_fmac_f32_e32 v2, v3, v2
	v_div_scale_f32 v3, vcc, 1.0, v0, 1.0
	v_mul_f32_e32 v4, v3, v2
	v_fma_f32 v5, -v1, v4, v3
	v_fmac_f32_e32 v4, v5, v2
	v_fma_f32 v1, -v1, v4, v3
	v_div_fmas_f32 v1, v1, v2, v4
	v_div_fixup_f32 v2, v1, v0, 1.0
	v_add_u32_e32 v0, 25, v34
	v_mul_f32_e32 v1, v13, v2
	v_cvt_pk_bf16_f32 v3, v1, s0
	v_ashrrev_i32_e32 v1, 31, v0
	v_lshlrev_b64 v[0:1], 10, v[0:1]
	v_mul_f32_e32 v2, v29, v2
	v_lshl_add_u64 v[0:1], v[32:33], 0, v[0:1]
	v_cvt_pk_bf16_f32 v2, v2, s0
	global_store_short v[0:1], v3, off
	global_store_short v[0:1], v2, off offset:64
	v_mov_b32_e32 v0, v115
	v_mov_b32_e32 v255, v115
	s_nop 1
	v_permlane16_swap_b32_e32 v0, v255
	s_nop 1
	v_add_f32_e32 v0, v0, v255
	s_nop 1
	v_mov_b32_dpp v1, v0 row_ror:8 row_mask:0xf bank_mask:0xf
	s_nop 0
	v_add_f32_e32 v0, v0, v1
	s_nop 1
	v_mov_b32_dpp v1, v0 row_shl:4 row_mask:0xf bank_mask:0x5
	v_mov_b32_dpp v1, v0 row_shr:4 row_mask:0xf bank_mask:0xa
	s_nop 0
	v_add_f32_e32 v0, v0, v1
	s_nop 1
	v_mov_b32_dpp v1, v0 quad_perm:[2,3,0,1] row_mask:0xf bank_mask:0xf
	v_add_f32_e32 v0, v0, v1
	s_nop 1
	v_add_f32_dpp v0, v0, v0 quad_perm:[1,0,3,2] row_mask:0xf bank_mask:0xf
	v_sub_f32_e32 v1, v146, v148
	v_mul_f32_e32 v1, 0x3fb8aa3b, v1
	v_exp_f32_e32 v1, v1
	s_nop 0
	v_add_f32_e32 v0, v1, v0
	v_div_scale_f32 v1, s[0:1], v0, v0, 1.0
	v_rcp_f32_e32 v2, v1
	s_nop 0
	v_fma_f32 v3, -v1, v2, 1.0
	v_fmac_f32_e32 v2, v3, v2
	v_div_scale_f32 v3, vcc, 1.0, v0, 1.0
	v_mul_f32_e32 v4, v3, v2
	v_fma_f32 v5, -v1, v4, v3
	v_fmac_f32_e32 v4, v5, v2
	v_fma_f32 v1, -v1, v4, v3
	v_div_fmas_f32 v1, v1, v2, v4
	v_div_fixup_f32 v2, v1, v0, 1.0
	v_add_u32_e32 v0, 26, v34
	v_mul_f32_e32 v1, v14, v2
	v_cvt_pk_bf16_f32 v3, v1, s0
	v_ashrrev_i32_e32 v1, 31, v0
	v_lshlrev_b64 v[0:1], 10, v[0:1]
	v_mul_f32_e32 v2, v30, v2
	v_lshl_add_u64 v[0:1], v[32:33], 0, v[0:1]
	v_cvt_pk_bf16_f32 v2, v2, s0
	global_store_short v[0:1], v3, off
	global_store_short v[0:1], v2, off offset:64
	v_mov_b32_e32 v0, v114
	v_mov_b32_e32 v255, v114
	s_nop 1
	v_permlane16_swap_b32_e32 v0, v255
	s_nop 1
	v_add_f32_e32 v0, v0, v255
	s_nop 1
	v_mov_b32_dpp v1, v0 row_ror:8 row_mask:0xf bank_mask:0xf
	s_nop 0
	v_add_f32_e32 v0, v0, v1
	s_nop 1
	v_mov_b32_dpp v1, v0 row_shl:4 row_mask:0xf bank_mask:0x5
	v_mov_b32_dpp v1, v0 row_shr:4 row_mask:0xf bank_mask:0xa
	s_nop 0
	v_add_f32_e32 v0, v0, v1
	s_nop 1
	v_mov_b32_dpp v1, v0 quad_perm:[2,3,0,1] row_mask:0xf bank_mask:0xf
	v_add_f32_e32 v0, v0, v1
	s_nop 1
	v_add_f32_dpp v0, v0, v0 quad_perm:[1,0,3,2] row_mask:0xf bank_mask:0xf
	v_sub_f32_e32 v1, v146, v147
	v_mul_f32_e32 v1, 0x3fb8aa3b, v1
	v_exp_f32_e32 v1, v1
	s_nop 0
	v_add_f32_e32 v0, v1, v0
	v_div_scale_f32 v1, s[0:1], v0, v0, 1.0
	v_rcp_f32_e32 v2, v1
	s_nop 0
	v_fma_f32 v3, -v1, v2, 1.0
	v_fmac_f32_e32 v2, v3, v2
	v_div_scale_f32 v3, vcc, 1.0, v0, 1.0
	v_mul_f32_e32 v4, v3, v2
	v_fma_f32 v5, -v1, v4, v3
	v_fmac_f32_e32 v4, v5, v2
	v_fma_f32 v1, -v1, v4, v3
	v_div_fmas_f32 v1, v1, v2, v4
	v_div_fixup_f32 v2, v1, v0, 1.0
	v_add_u32_e32 v0, 27, v34
	v_mul_f32_e32 v1, v15, v2
	v_cvt_pk_bf16_f32 v3, v1, s0
	v_ashrrev_i32_e32 v1, 31, v0
	v_lshlrev_b64 v[0:1], 10, v[0:1]
	v_mul_f32_e32 v2, v31, v2
	v_lshl_add_u64 v[0:1], v[32:33], 0, v[0:1]
	v_cvt_pk_bf16_f32 v2, v2, s0
	s_mov_b64 s[0:1], 0
	global_store_short v[0:1], v3, off
	global_store_short v[0:1], v2, off offset:64

.LBB0_859:
	v_add_u32_e32 v67, v65, v64
	ds_read_b128 v[76:79], v65 offset:18432
	ds_read_b128 v[80:83], v67
	s_add_i32 s0, s0, 32
	s_cmp_lt_u32 s0, 48
	s_waitcnt lgkmcnt(0)
	v_mfma_f32_32x32x16_bf16 v[48:63], v[80:83], v[76:79], v[48:63]
	ds_read_b128 v[76:79], v65 offset:23040
	s_waitcnt lgkmcnt(0)
	v_mfma_f32_32x32x16_bf16 v[16:31], v[80:83], v[76:79], v[16:31]
	ds_read_b128 v[76:79], v65 offset:27648
	s_waitcnt lgkmcnt(0)
	v_mfma_f32_32x32x16_bf16 v[32:47], v[80:83], v[76:79], v[32:47]
	ds_read_b128 v[76:79], v65 offset:32256
	ds_read_b128 v[84:87], v65 offset:18464
	s_waitcnt lgkmcnt(1)
	v_mfma_f32_32x32x16_bf16 v[0:15], v[80:83], v[76:79], v[0:15]
	ds_read_b128 v[76:79], v67 offset:32
	ds_read_b128 v[80:83], v65 offset:23072
	s_waitcnt lgkmcnt(0)
	v_mfma_f32_32x32x16_bf16 v[16:31], v[76:79], v[80:83], v[16:31]
	ds_read_b128 v[80:83], v65 offset:27680
	s_waitcnt lgkmcnt(0)
	v_mfma_f32_32x32x16_bf16 v[32:47], v[76:79], v[80:83], v[32:47]
	ds_read_b128 v[80:83], v65 offset:32288
	v_add_u32_e32 v65, 64, v65
	v_mfma_f32_32x32x16_bf16 v[48:63], v[76:79], v[84:87], v[48:63]
	s_waitcnt lgkmcnt(0)
	v_mfma_f32_32x32x16_bf16 v[0:15], v[76:79], v[80:83], v[0:15]
	s_cbranch_scc1 .LBB0_859
	v_and_b32_e32 v141, 63, v72
	v_or_b32_e32 v140, s13, v141
	v_readlane_b32 s0, v249, 15
	v_lshlrev_b32_e32 v96, 3, v140
	v_readlane_b32 s1, v249, 16
	v_readlane_b32 s16, v251, 20
	v_lshlrev_b32_e32 v69, 11, v66
	v_lshl_add_u64 v[64:65], s[0:1], 0, v[96:97]
	v_readlane_b32 s0, v248, 25
	s_or_b32 s3, s13, s0
	v_or_b32_e32 v96, s3, v74
	v_lshlrev_b64 v[66:67], 2, v[96:97]
	v_readlane_b32 s18, v251, 22
	v_readlane_b32 s19, v251, 23
	s_barrier
	s_nop 0
	v_lshl_add_u64 v[70:71], s[18:19], 0, v[66:67]
	v_readlane_b32 s100, v251, 16
	v_readlane_b32 s101, v251, 17
	s_nop 1
	v_lshl_add_u64 v[220:221], s[100:101], 0, v[66:67]
	v_readlane_b32 s100, v251, 20
	v_readlane_b32 s101, v251, 21
	s_nop 1
	v_lshl_add_u64 v[222:223], s[100:101], 0, v[66:67]
	global_load_dword v224, v[220:221], off
	global_load_dword v225, v[222:223], off
	global_load_dword v226, v[70:71], off offset:128
	global_load_dword v227, v[222:223], off offset:128
	global_load_dword v228, v[220:221], off offset:128
	global_load_dword v70, v[70:71], off
	s_mov_b32 s4, 0x3f2aaaab
	s_mov_b32 s8, 0x3f317218
	v_readlane_b32 s40, v251, 4
	v_readlane_b32 s52, v251, 16
	v_readlane_b32 s53, v251, 17
	v_readlane_b32 s17, v251, 21
	s_mov_b32 s9, 0x7f800000
	s_mov_b32 s10, 0x33800000
	v_readlane_b32 s20, v251, 24
	s_mov_b32 s20, 0x43000000
	v_readlane_b32 s21, v251, 25
	s_mov_b32 s21, 0x42b17217
	v_readlane_b32 s22, v251, 26
	s_mov_b32 s22, 0xf800000
	v_readlane_b32 s23, v251, 27
	s_mov_b32 s23, 0xc1880000
	v_add_u32_e32 v96, s3, v74
	s_mov_b32 s2, 0
	s_cmp_eq_u32 s12, 0
	v_readlane_b32 s24, v251, 28
	v_readlane_b32 s25, v251, 29
	v_readlane_b32 s26, v251, 30
	v_readlane_b32 s27, v251, 31
	v_readlane_b32 s28, v251, 32
	v_readlane_b32 s29, v251, 33
	v_readlane_b32 s30, v251, 34
	v_readlane_b32 s31, v251, 35
	v_readlane_b32 s41, v251, 5
	v_readlane_b32 s42, v251, 6
	v_readlane_b32 s43, v251, 7
	v_readlane_b32 s44, v251, 8
	v_readlane_b32 s45, v251, 9
	v_readlane_b32 s46, v251, 10
	v_readlane_b32 s47, v251, 11
	v_readlane_b32 s48, v251, 12
	v_readlane_b32 s49, v251, 13
	v_readlane_b32 s50, v251, 14
	v_readlane_b32 s51, v251, 15
	v_readlane_b32 s54, v251, 18
	v_readlane_b32 s55, v251, 19
	s_waitcnt vmcnt(0)
	v_mul_f32_e32 v70, 0xbfb8aa3b, v70
	v_exp_f32_e32 v73, v70
	s_nop 0
	v_add_f32_e32 v75, 1.0, v73
	v_add_f32_e32 v70, -1.0, v75
	v_sub_f32_e32 v71, v70, v75
	v_add_f32_e32 v71, 1.0, v71
	v_sub_f32_e32 v70, v73, v70
	v_add_f32_e32 v76, v70, v71
	v_frexp_mant_f32_e32 v70, v75
	v_cmp_gt_f32_e32 vcc, s4, v70
	v_cvt_f64_f32_e32 v[70:71], v75
	v_frexp_exp_i32_f64_e32 v70, v[70:71]
	v_subbrev_co_u32_e32 v82, vcc, 0, v70, vcc
	v_sub_u32_e32 v70, 0, v82
	v_ldexp_f32 v71, v75, v70
	v_add_f32_e32 v75, -1.0, v71
	v_add_f32_e32 v77, 1.0, v71
	v_ldexp_f32 v70, v76, v70
	v_add_f32_e32 v76, 1.0, v75
	v_add_f32_e32 v78, -1.0, v77
	v_sub_f32_e32 v76, v71, v76
	v_sub_f32_e32 v71, v71, v78
	v_add_f32_e32 v76, v70, v76
	v_add_f32_e32 v70, v70, v71
	v_add_f32_e32 v83, v77, v70
	v_rcp_f32_e32 v85, v83
	v_sub_f32_e32 v71, v83, v77
	v_sub_f32_e32 v84, v70, v71
	v_add_f32_e32 v71, v75, v76
	v_sub_f32_e32 v70, v71, v75
	v_mul_f32_e32 v86, v71, v85
	v_sub_f32_e32 v75, v76, v70
	v_mul_f32_e32 v76, v83, v86
	v_fma_f32 v78, v86, v83, -v76
	v_fmac_f32_e32 v78, v86, v84
	v_add_f32_e32 v70, v76, v78
	v_sub_f32_e32 v77, v71, v70
	v_pk_add_f32 v[80:81], v[70:71], v[76:77] neg_lo:[0,1] neg_hi:[0,1]
	v_mov_b32_e32 v79, v70
	v_pk_add_f32 v[70:71], v[80:81], v[78:79] neg_lo:[0,1] neg_hi:[0,1]
	v_cmp_neq_f32_e32 vcc, s9, v73
	v_add_f32_e32 v71, v75, v71
	v_add_f32_e32 v70, v70, v71
	v_add_f32_e32 v71, v77, v70
	v_mul_f32_e32 v75, v85, v71
	v_mul_f32_e32 v76, v83, v75
	v_fma_f32 v78, v75, v83, -v76
	v_fmac_f32_e32 v78, v75, v84
	v_sub_f32_e32 v77, v77, v71
	v_add_f32_e32 v83, v70, v77
	v_add_f32_e32 v70, v76, v78
	v_sub_f32_e32 v77, v71, v70
	v_pk_add_f32 v[80:81], v[70:71], v[76:77] neg_lo:[0,1] neg_hi:[0,1]
	v_mov_b32_e32 v79, v70
	v_pk_add_f32 v[70:71], v[80:81], v[78:79] neg_lo:[0,1] neg_hi:[0,1]
	v_add_f32_e32 v71, v83, v71
	v_add_f32_e32 v70, v70, v71
	v_add_f32_e32 v71, v86, v75
	v_add_f32_e32 v70, v77, v70
	v_sub_f32_e32 v76, v71, v86
	v_mul_f32_e32 v70, v85, v70
	v_sub_f32_e32 v75, v75, v76
	v_add_f32_e32 v75, v75, v70
	v_add_f32_e32 v76, v71, v75
	v_mul_f32_e32 v78, v76, v76
	v_fmamk_f32 v70, v78, 0x3e9b6dac, v191
	v_fmaak_f32 v169, v78, v70, 0x3f2aaada
	v_cvt_f32_i32_e32 v70, v82
	v_sub_f32_e32 v71, v76, v71
	v_sub_f32_e32 v71, v75, v71
	v_ldexp_f32 v75, v71, 1
	v_mul_f32_e32 v71, v76, v78
	v_pk_mul_f32 v[78:79], v[70:71], v[168:169]
	v_ldexp_f32 v77, v76, 1
	v_fma_f32 v76, v70, s8, -v78
	v_fmac_f32_e32 v76, 0xb102e308, v70
	v_pk_add_f32 v[70:71], v[78:79], v[76:77]
	v_mov_b32_e32 v80, v78
	v_sub_f32_e32 v77, v71, v77
	v_sub_f32_e32 v77, v79, v77
	v_add_f32_e32 v81, v75, v77
	v_pk_add_f32 v[78:79], v[70:71], v[78:79] neg_lo:[0,1] neg_hi:[0,1]
	v_pk_add_f32 v[82:83], v[70:71], v[80:81]
	v_mov_b32_e32 v77, v70
	v_mov_b32_e32 v79, v83
	v_pk_add_f32 v[84:85], v[76:77], v[78:79] neg_lo:[0,1] neg_hi:[0,1]
	v_pk_add_f32 v[76:77], v[76:77], v[78:79]
	v_mov_b32_e32 v80, v81
	v_pk_add_f32 v[78:79], v[76:77], v[70:71] op_sel:[1,0] op_sel_hi:[0,1] neg_lo:[0,1] neg_hi:[0,1]
	v_pk_add_f32 v[86:87], v[82:83], v[78:79] op_sel_hi:[1,0] neg_lo:[0,1] neg_hi:[0,1]
	v_mov_b32_e32 v82, v83
	v_mov_b32_e32 v83, v77
	v_pk_mov_b32 v[78:79], v[70:71], v[78:79] op_sel:[1,0]
	v_mov_b32_e32 v81, v70
	v_pk_add_f32 v[78:79], v[82:83], v[78:79] neg_lo:[0,1] neg_hi:[0,1]
	v_mov_b32_e32 v86, v84
	v_pk_add_f32 v[70:71], v[80:81], v[78:79] neg_lo:[0,1] neg_hi:[0,1]
	v_mov_b32_e32 v85, v77
	v_pk_add_f32 v[78:79], v[86:87], v[70:71]
	v_pk_add_f32 v[80:81], v[78:79], v[78:79] op_sel:[0,1] op_sel_hi:[1,0]
	v_pk_add_f32 v[76:77], v[76:77], v[80:81] op_sel:[1,0] op_sel_hi:[0,1]
	v_mov_b32_e32 v79, v76
	v_pk_add_f32 v[82:83], v[78:79], v[84:85] neg_lo:[0,1] neg_hi:[0,1]
	v_mov_b32_e32 v71, v80
	v_sub_f32_e32 v75, v78, v82
	v_pk_add_f32 v[70:71], v[70:71], v[82:83] neg_lo:[0,1] neg_hi:[0,1]
	v_sub_f32_e32 v75, v84, v75
	v_add_f32_e32 v70, v70, v75
	v_add_f32_e32 v70, v70, v71
	v_add_f32_e32 v70, v76, v70
	v_lshl_add_u64 v[76:77], s[52:53], 0, v[66:67]
	v_mov_b32_e32 v77, v224
	v_lshl_add_u64 v[66:67], s[16:17], 0, v[66:67]
	v_mov_b32_e32 v76, v225
	v_cndmask_b32_e32 v70, v199, v70, vcc
	v_cmp_ngt_f32_e32 vcc, -1.0, v73
	s_waitcnt vmcnt(1)
	v_add_f32_e32 v48, v48, v77
	v_mul_f32_e32 v48, 0xbfb8aa3b, v48
	v_exp_f32_e32 v48, v48
	v_cndmask_b32_e32 v70, v200, v70, vcc
	v_cmp_neq_f32_e32 vcc, -1.0, v73
	s_waitcnt vmcnt(0)
	v_add_f32_e32 v32, v32, v76
	v_add_f32_e32 v48, 1.0, v48
	v_rcp_f32_e32 v48, v48
	v_cndmask_b32_e32 v70, v201, v70, vcc
	v_cmp_lt_f32_e64 vcc, |v73|, s10
	v_mul_f32_e32 v32, 0xbfb8aa3b, v32
	v_exp_f32_e32 v32, v32
	v_cndmask_b32_e32 v70, v70, v73, vcc
	v_mul_f32_e32 v75, 0xc1000000, v70
	v_mul_f32_e32 v48, v48, v75
	v_mul_f32_e32 v66, 0x3fb8aa3b, v48
	v_add_f32_e32 v48, v48, v48
	v_exp_f32_e32 v70, v66
	v_mul_f32_e32 v66, 0x3fb8aa3b, v48
	v_rndne_f32_e32 v66, v66
	v_fmamk_f32 v67, v66, 0xbf317218, v48
	v_fmac_f32_e32 v67, 0x3102e308, v66
	v_fmamk_f32 v71, v67, 0x395133b1, v192
	v_cmp_eq_f32_e32 vcc, s20, v66
	v_cvt_i32_f32_e32 v66, v66
	v_fmaak_f32 v71, v67, v71, 0x3c0887f9
	v_fmaak_f32 v71, v67, v71, 0x3d2aaa81
	v_fmaak_f32 v71, v67, v71, 0x3e2aaaab
	v_fma_f32 v71, v67, v71, 0.5
	v_ldexp_f32 v66, 1.0, v66
	v_mul_f32_e32 v71, v67, v71
	v_cndmask_b32_e32 v66, v66, v202, vcc
	v_fmac_f32_e32 v67, v67, v71
	v_add_f32_e32 v71, -1.0, v66
	v_fmac_f32_e32 v71, v66, v67
	v_add_f32_e32 v66, v71, v71
	v_cndmask_b32_e32 v66, v71, v66, vcc
	v_cmp_nlt_f32_e32 vcc, s21, v48
	v_add_f32_e32 v32, 1.0, v32
	v_rcp_f32_e32 v32, v32
	v_cndmask_b32_e64 v66, v201, -v66, vcc
	v_cmp_gt_f32_e32 vcc, s22, v66
	v_mul_f32_e32 v67, 0x4f800000, v66
	v_add_f32_e32 v33, v33, v76
	v_cndmask_b32_e32 v66, v66, v67, vcc
	v_sqrt_f32_e32 v67, v66
	v_mul_f32_e32 v33, 0xbfb8aa3b, v33
	v_exp_f32_e32 v33, v33
	v_add_f32_e32 v34, v34, v76
	v_add_u32_e32 v71, -1, v67
	v_fma_f32 v73, -v71, v67, v66
	v_cmp_ge_f32_e64 s[0:1], 0, v73
	v_add_u32_e32 v73, 1, v67
	v_add_f32_e32 v33, 1.0, v33
	v_cndmask_b32_e64 v71, v67, v71, s[0:1]
	v_fma_f32 v67, -v73, v67, v66
	v_cmp_lt_f32_e64 s[0:1], 0, v67
	v_rcp_f32_e32 v33, v33
	v_mul_f32_e32 v34, 0xbfb8aa3b, v34
	v_cndmask_b32_e64 v67, v71, v73, s[0:1]
	v_mul_f32_e32 v71, 0x37800000, v67
	v_cndmask_b32_e32 v67, v67, v71, vcc
	v_cmp_class_f32_e32 vcc, v66, v193
	v_exp_f32_e32 v34, v34
	s_nop 0
	v_cndmask_b32_e32 v66, v67, v66, vcc
	v_cmp_ngt_f32_e32 vcc, s23, v48
	v_add_f32_e32 v34, 1.0, v34
	v_rcp_f32_e32 v34, v34
	v_cndmask_b32_e32 v48, 1.0, v66, vcc
	v_mul_f32_e32 v48, v32, v48
	v_and_b32_e32 v32, 0x100, v68
	v_or3_b32 v32, v69, v74, v32
	v_lshl_add_u32 v73, v32, 2, 0
	v_add_u32_e32 v32, 0x9000, v73
	ds_read2_b32 v[66:67], v32 offset1:32
	s_waitcnt lgkmcnt(0)
	v_mul_f32_e32 v48, v66, v48
	ds_write_b32 v73, v70
	ds_write_b32 v73, v48 offset:36864
	v_add_f32_e32 v48, v49, v77
	v_mul_f32_e32 v48, 0xbfb8aa3b, v48
	v_exp_f32_e32 v48, v48
	s_nop 0
	v_add_f32_e32 v48, 1.0, v48
	v_rcp_f32_e32 v48, v48
	s_nop 0
	v_mul_f32_e32 v48, v48, v75
	v_mul_f32_e32 v49, 0x3fb8aa3b, v48
	v_add_f32_e32 v48, v48, v48
	v_exp_f32_e32 v66, v49
	v_mul_f32_e32 v49, 0x3fb8aa3b, v48
	v_rndne_f32_e32 v49, v49
	v_fmamk_f32 v68, v49, 0xbf317218, v48
	v_fmac_f32_e32 v68, 0x3102e308, v49
	v_fmamk_f32 v69, v68, 0x395133b1, v192
	v_cmp_eq_f32_e32 vcc, s20, v49
	v_cvt_i32_f32_e32 v49, v49
	v_fmaak_f32 v69, v68, v69, 0x3c0887f9
	v_fmaak_f32 v69, v68, v69, 0x3d2aaa81
	v_fmaak_f32 v69, v68, v69, 0x3e2aaaab
	v_fma_f32 v69, v68, v69, 0.5
	v_ldexp_f32 v49, 1.0, v49
	v_mul_f32_e32 v69, v68, v69
	v_cndmask_b32_e32 v49, v49, v202, vcc
	v_fmac_f32_e32 v68, v68, v69
	v_add_f32_e32 v69, -1.0, v49
	v_fmac_f32_e32 v69, v49, v68
	v_add_f32_e32 v49, v69, v69
	v_cndmask_b32_e32 v49, v69, v49, vcc
	v_cmp_nlt_f32_e32 vcc, s21, v48
	s_nop 1
	v_cndmask_b32_e64 v49, v201, -v49, vcc
	v_cmp_gt_f32_e32 vcc, s22, v49
	v_mul_f32_e32 v68, 0x4f800000, v49
	s_nop 0
	v_cndmask_b32_e32 v49, v49, v68, vcc
	v_sqrt_f32_e32 v68, v49
	s_nop 0
	v_add_u32_e32 v69, -1, v68
	v_fma_f32 v70, -v69, v68, v49
	v_cmp_ge_f32_e64 s[0:1], 0, v70
	v_add_u32_e32 v70, 1, v68
	s_nop 0
	v_cndmask_b32_e64 v69, v68, v69, s[0:1]
	v_fma_f32 v68, -v70, v68, v49
	v_cmp_lt_f32_e64 s[0:1], 0, v68
	s_nop 1
	v_cndmask_b32_e64 v68, v69, v70, s[0:1]
	v_mul_f32_e32 v69, 0x37800000, v68
	v_cndmask_b32_e32 v68, v68, v69, vcc
	v_cmp_class_f32_e32 vcc, v49, v193
	s_nop 1
	v_cndmask_b32_e32 v49, v68, v49, vcc
	v_cmp_ngt_f32_e32 vcc, s23, v48
	s_nop 1
	v_cndmask_b32_e32 v48, 1.0, v49, vcc
	v_mul_f32_e32 v33, v33, v48
	ds_read2_b32 v[48:49], v32 offset0:64 offset1:96
	s_waitcnt lgkmcnt(0)
	v_mul_f32_e32 v33, v48, v33
	ds_write_b32 v73, v66 offset:256
	ds_write_b32 v73, v33 offset:37120
	v_add_f32_e32 v33, v50, v77
	v_mul_f32_e32 v33, 0xbfb8aa3b, v33
	v_exp_f32_e32 v33, v33
	s_nop 0
	v_add_f32_e32 v33, 1.0, v33
	v_rcp_f32_e32 v33, v33
	s_nop 0
	v_mul_f32_e32 v33, v33, v75
	v_mul_f32_e32 v48, 0x3fb8aa3b, v33
	v_add_f32_e32 v33, v33, v33
	v_mul_f32_e32 v50, 0x3fb8aa3b, v33
	v_rndne_f32_e32 v50, v50
	v_fmamk_f32 v66, v50, 0xbf317218, v33
	v_fmac_f32_e32 v66, 0x3102e308, v50
	v_fmamk_f32 v68, v66, 0x395133b1, v192
	v_cmp_eq_f32_e32 vcc, s20, v50
	v_cvt_i32_f32_e32 v50, v50
	v_fmaak_f32 v68, v66, v68, 0x3c0887f9
	v_fmaak_f32 v68, v66, v68, 0x3d2aaa81
	v_fmaak_f32 v68, v66, v68, 0x3e2aaaab
	v_fma_f32 v68, v66, v68, 0.5
	v_ldexp_f32 v50, 1.0, v50
	v_mul_f32_e32 v68, v66, v68
	v_cndmask_b32_e32 v50, v50, v202, vcc
	v_fmac_f32_e32 v66, v66, v68
	v_add_f32_e32 v68, -1.0, v50
	v_fmac_f32_e32 v68, v50, v66
	v_add_f32_e32 v50, v68, v68
	v_cndmask_b32_e32 v50, v68, v50, vcc
	v_cmp_nlt_f32_e32 vcc, s21, v33
	v_exp_f32_e32 v48, v48
	s_nop 0
	v_cndmask_b32_e64 v50, v201, -v50, vcc
	v_cmp_gt_f32_e32 vcc, s22, v50
	v_mul_f32_e32 v66, 0x4f800000, v50
	s_nop 0
	v_cndmask_b32_e32 v50, v50, v66, vcc
	v_sqrt_f32_e32 v66, v50
	s_nop 0
	v_add_u32_e32 v68, -1, v66
	v_fma_f32 v69, -v68, v66, v50
	v_cmp_ge_f32_e64 s[0:1], 0, v69
	v_add_u32_e32 v69, 1, v66
	s_nop 0
	v_cndmask_b32_e64 v68, v66, v68, s[0:1]
	v_fma_f32 v66, -v69, v66, v50
	v_cmp_lt_f32_e64 s[0:1], 0, v66
	s_nop 1
	v_cndmask_b32_e64 v66, v68, v69, s[0:1]
	v_mul_f32_e32 v68, 0x37800000, v66
	v_cndmask_b32_e32 v66, v66, v68, vcc
	ds_read2_b32 v[68:69], v32 offset0:128 offset1:160
	v_cmp_class_f32_e32 vcc, v50, v193
	s_nop 1
	v_cndmask_b32_e32 v50, v66, v50, vcc
	v_cmp_ngt_f32_e32 vcc, s23, v33
	s_nop 1
	v_cndmask_b32_e32 v33, 1.0, v50, vcc
	v_mul_f32_e32 v33, v34, v33
	s_waitcnt lgkmcnt(0)
	v_mul_f32_e32 v33, v68, v33
	ds_write_b32 v73, v48 offset:512
	ds_write_b32 v73, v33 offset:37376
	v_add_f32_e32 v33, v51, v77
	v_mul_f32_e32 v33, 0xbfb8aa3b, v33
	v_exp_f32_e32 v33, v33
	v_add_f32_e32 v34, v35, v76
	v_mul_f32_e32 v34, 0xbfb8aa3b, v34
	v_exp_f32_e32 v34, v34
	v_add_f32_e32 v33, 1.0, v33
	v_rcp_f32_e32 v33, v33
	v_add_f32_e32 v34, 1.0, v34
	v_rcp_f32_e32 v34, v34
	v_mul_f32_e32 v33, v33, v75
	v_mul_f32_e32 v35, 0x3fb8aa3b, v33
	v_add_f32_e32 v33, v33, v33
	v_mul_f32_e32 v48, 0x3fb8aa3b, v33
	v_rndne_f32_e32 v48, v48
	v_fmamk_f32 v50, v48, 0xbf317218, v33
	v_fmac_f32_e32 v50, 0x3102e308, v48
	v_fmamk_f32 v51, v50, 0x395133b1, v192
	v_cmp_eq_f32_e32 vcc, s20, v48
	v_cvt_i32_f32_e32 v48, v48
	v_fmaak_f32 v51, v50, v51, 0x3c0887f9
	v_fmaak_f32 v51, v50, v51, 0x3d2aaa81
	v_fmaak_f32 v51, v50, v51, 0x3e2aaaab
	v_fma_f32 v51, v50, v51, 0.5
	v_ldexp_f32 v48, 1.0, v48
	v_mul_f32_e32 v51, v50, v51
	v_cndmask_b32_e32 v48, v48, v202, vcc
	v_fmac_f32_e32 v50, v50, v51
	v_add_f32_e32 v51, -1.0, v48
	v_fmac_f32_e32 v51, v48, v50
	v_add_f32_e32 v48, v51, v51
	v_cndmask_b32_e32 v48, v51, v48, vcc
	v_cmp_nlt_f32_e32 vcc, s21, v33
	v_exp_f32_e32 v35, v35
	s_nop 0
	v_cndmask_b32_e64 v48, v201, -v48, vcc
	v_cmp_gt_f32_e32 vcc, s22, v48
	v_mul_f32_e32 v50, 0x4f800000, v48
	s_nop 0
	v_cndmask_b32_e32 v48, v48, v50, vcc
	v_sqrt_f32_e32 v50, v48
	s_nop 0
	v_add_u32_e32 v51, -1, v50
	v_fma_f32 v66, -v51, v50, v48
	v_cmp_ge_f32_e64 s[0:1], 0, v66
	v_add_u32_e32 v66, 1, v50
	s_nop 0
	v_cndmask_b32_e64 v51, v50, v51, s[0:1]
	v_fma_f32 v50, -v66, v50, v48
	v_cmp_lt_f32_e64 s[0:1], 0, v50
	s_nop 1
	v_cndmask_b32_e64 v50, v51, v66, s[0:1]
	v_mul_f32_e32 v51, 0x37800000, v50
	v_cndmask_b32_e32 v50, v50, v51, vcc
	v_cmp_class_f32_e32 vcc, v48, v193
	s_nop 1
	v_cndmask_b32_e32 v48, v50, v48, vcc
	ds_read2_b32 v[50:51], v32 offset0:192 offset1:224
	v_cmp_ngt_f32_e32 vcc, s23, v33
	s_nop 1
	v_cndmask_b32_e32 v33, 1.0, v48, vcc
	v_mul_f32_e32 v33, v34, v33
	s_waitcnt lgkmcnt(0)
	v_mul_f32_e32 v32, v50, v33
	ds_write_b32 v73, v35 offset:768
	ds_write_b32 v73, v32 offset:37632
	v_add_f32_e32 v32, v52, v77
	v_mul_f32_e32 v32, 0xbfb8aa3b, v32
	v_exp_f32_e32 v32, v32
	v_add_f32_e32 v33, v36, v76
	v_mul_f32_e32 v33, 0xbfb8aa3b, v33
	v_exp_f32_e32 v33, v33
	v_add_f32_e32 v32, 1.0, v32
	v_rcp_f32_e32 v32, v32
	v_add_f32_e32 v33, 1.0, v33
	v_rcp_f32_e32 v33, v33
	v_mul_f32_e32 v32, v32, v75
	v_mul_f32_e32 v34, 0x3fb8aa3b, v32
	v_add_f32_e32 v32, v32, v32
	v_mul_f32_e32 v35, 0x3fb8aa3b, v32
	v_rndne_f32_e32 v35, v35
	v_fmamk_f32 v36, v35, 0xbf317218, v32
	v_fmac_f32_e32 v36, 0x3102e308, v35
	v_fmamk_f32 v48, v36, 0x395133b1, v192
	v_cmp_eq_f32_e32 vcc, s20, v35
	v_cvt_i32_f32_e32 v35, v35
	v_fmaak_f32 v48, v36, v48, 0x3c0887f9
	v_fmaak_f32 v48, v36, v48, 0x3d2aaa81
	v_fmaak_f32 v48, v36, v48, 0x3e2aaaab
	v_fma_f32 v48, v36, v48, 0.5
	v_ldexp_f32 v35, 1.0, v35
	v_mul_f32_e32 v48, v36, v48
	v_cndmask_b32_e32 v35, v35, v202, vcc
	v_fmac_f32_e32 v36, v36, v48
	v_add_f32_e32 v48, -1.0, v35
	v_fmac_f32_e32 v48, v35, v36
	v_add_f32_e32 v35, v48, v48
	v_cndmask_b32_e32 v35, v48, v35, vcc
	v_cmp_nlt_f32_e32 vcc, s21, v32
	v_exp_f32_e32 v34, v34
	s_nop 0
	v_cndmask_b32_e64 v35, v201, -v35, vcc
	v_cmp_gt_f32_e32 vcc, s22, v35
	v_mul_f32_e32 v36, 0x4f800000, v35
	s_nop 0
	v_cndmask_b32_e32 v35, v35, v36, vcc
	v_sqrt_f32_e32 v36, v35
	s_nop 0
	v_add_u32_e32 v48, -1, v36
	v_fma_f32 v50, -v48, v36, v35
	v_cmp_ge_f32_e64 s[0:1], 0, v50
	v_add_u32_e32 v50, 1, v36
	s_nop 0
	v_cndmask_b32_e64 v48, v36, v48, s[0:1]
	v_fma_f32 v36, -v50, v36, v35
	v_cmp_lt_f32_e64 s[0:1], 0, v36
	s_nop 1
	v_cndmask_b32_e64 v36, v48, v50, s[0:1]
	v_mul_f32_e32 v48, 0x37800000, v36
	v_cndmask_b32_e32 v36, v36, v48, vcc
	v_cmp_class_f32_e32 vcc, v35, v193
	s_nop 1
	v_cndmask_b32_e32 v35, v36, v35, vcc
	v_cmp_ngt_f32_e32 vcc, s23, v32
	s_nop 1
	v_cndmask_b32_e32 v32, 1.0, v35, vcc
	v_mul_f32_e32 v33, v33, v32
	v_add_u32_e32 v32, 0x9800, v73
	ds_read2_b32 v[70:71], v32 offset1:32
	s_waitcnt lgkmcnt(0)
	v_mul_f32_e32 v33, v70, v33
	ds_write_b32 v73, v34 offset:2048
	ds_write_b32 v73, v33 offset:38912
	v_add_f32_e32 v33, v53, v77
	v_mul_f32_e32 v33, 0xbfb8aa3b, v33
	v_exp_f32_e32 v33, v33
	v_add_f32_e32 v34, v37, v76
	v_mul_f32_e32 v34, 0xbfb8aa3b, v34
	v_exp_f32_e32 v34, v34
	v_add_f32_e32 v33, 1.0, v33
	v_rcp_f32_e32 v33, v33
	v_add_f32_e32 v34, 1.0, v34
	v_rcp_f32_e32 v34, v34
	v_mul_f32_e32 v33, v33, v75
	v_mul_f32_e32 v35, 0x3fb8aa3b, v33
	v_add_f32_e32 v33, v33, v33
	v_mul_f32_e32 v36, 0x3fb8aa3b, v33
	v_rndne_f32_e32 v36, v36
	v_fmamk_f32 v37, v36, 0xbf317218, v33
	v_fmac_f32_e32 v37, 0x3102e308, v36
	v_fmamk_f32 v48, v37, 0x395133b1, v192
	v_cmp_eq_f32_e32 vcc, s20, v36
	v_cvt_i32_f32_e32 v36, v36
	v_fmaak_f32 v48, v37, v48, 0x3c0887f9
	v_fmaak_f32 v48, v37, v48, 0x3d2aaa81
	v_fmaak_f32 v48, v37, v48, 0x3e2aaaab
	v_fma_f32 v48, v37, v48, 0.5
	v_ldexp_f32 v36, 1.0, v36
	v_mul_f32_e32 v48, v37, v48
	v_cndmask_b32_e32 v36, v36, v202, vcc
	v_fmac_f32_e32 v37, v37, v48
	v_add_f32_e32 v48, -1.0, v36
	v_fmac_f32_e32 v48, v36, v37
	v_add_f32_e32 v36, v48, v48
	v_cndmask_b32_e32 v36, v48, v36, vcc
	v_cmp_nlt_f32_e32 vcc, s21, v33
	v_exp_f32_e32 v35, v35
	s_nop 0
	v_cndmask_b32_e64 v36, v201, -v36, vcc
	v_cmp_gt_f32_e32 vcc, s22, v36
	v_mul_f32_e32 v37, 0x4f800000, v36
	s_nop 0
	v_cndmask_b32_e32 v36, v36, v37, vcc
	v_sqrt_f32_e32 v37, v36
	s_nop 0
	v_add_u32_e32 v48, -1, v37
	v_fma_f32 v50, -v48, v37, v36
	v_cmp_ge_f32_e64 s[0:1], 0, v50
	v_add_u32_e32 v50, 1, v37
	s_nop 0
	v_cndmask_b32_e64 v48, v37, v48, s[0:1]
	v_fma_f32 v37, -v50, v37, v36
	v_cmp_lt_f32_e64 s[0:1], 0, v37
	s_nop 1
	v_cndmask_b32_e64 v37, v48, v50, s[0:1]
	v_mul_f32_e32 v48, 0x37800000, v37
	v_cndmask_b32_e32 v37, v37, v48, vcc
	v_cmp_class_f32_e32 vcc, v36, v193
	s_nop 1
	v_cndmask_b32_e32 v36, v37, v36, vcc
	v_cmp_ngt_f32_e32 vcc, s23, v33
	s_nop 1
	v_cndmask_b32_e32 v33, 1.0, v36, vcc
	ds_read2_b32 v[36:37], v32 offset0:64 offset1:96
	v_mul_f32_e32 v33, v34, v33
	v_add_f32_e32 v34, v38, v76
	v_mul_f32_e32 v34, 0xbfb8aa3b, v34
	v_exp_f32_e32 v34, v34
	s_waitcnt lgkmcnt(0)
	v_mul_f32_e32 v33, v36, v33
	ds_write_b32 v73, v35 offset:2304
	ds_write_b32 v73, v33 offset:39168
	v_add_f32_e32 v33, v54, v77
	v_mul_f32_e32 v33, 0xbfb8aa3b, v33
	v_exp_f32_e32 v33, v33
	v_add_f32_e32 v34, 1.0, v34
	v_rcp_f32_e32 v34, v34
	ds_read2_b32 v[52:53], v32 offset0:128 offset1:160
	v_add_f32_e32 v33, 1.0, v33
	v_rcp_f32_e32 v33, v33
	s_nop 0
	v_mul_f32_e32 v33, v33, v75
	v_mul_f32_e32 v35, 0x3fb8aa3b, v33
	v_add_f32_e32 v33, v33, v33
	v_mul_f32_e32 v36, 0x3fb8aa3b, v33
	v_rndne_f32_e32 v36, v36
	v_fmamk_f32 v38, v36, 0xbf317218, v33
	v_fmac_f32_e32 v38, 0x3102e308, v36
	v_fmamk_f32 v48, v38, 0x395133b1, v192
	v_cmp_eq_f32_e32 vcc, s20, v36
	v_cvt_i32_f32_e32 v36, v36
	v_fmaak_f32 v48, v38, v48, 0x3c0887f9
	v_fmaak_f32 v48, v38, v48, 0x3d2aaa81
	v_fmaak_f32 v48, v38, v48, 0x3e2aaaab
	v_fma_f32 v48, v38, v48, 0.5
	v_ldexp_f32 v36, 1.0, v36
	v_mul_f32_e32 v48, v38, v48
	v_cndmask_b32_e32 v36, v36, v202, vcc
	v_fmac_f32_e32 v38, v38, v48
	v_add_f32_e32 v48, -1.0, v36
	v_fmac_f32_e32 v48, v36, v38
	v_add_f32_e32 v36, v48, v48
	v_cndmask_b32_e32 v36, v48, v36, vcc
	v_cmp_nlt_f32_e32 vcc, s21, v33
	v_exp_f32_e32 v35, v35
	s_nop 0
	v_cndmask_b32_e64 v36, v201, -v36, vcc
	v_cmp_gt_f32_e32 vcc, s22, v36
	v_mul_f32_e32 v38, 0x4f800000, v36
	s_nop 0
	v_cndmask_b32_e32 v36, v36, v38, vcc
	v_sqrt_f32_e32 v38, v36
	s_nop 0
	v_add_u32_e32 v48, -1, v38
	v_fma_f32 v50, -v48, v38, v36
	v_cmp_ge_f32_e64 s[0:1], 0, v50
	v_add_u32_e32 v50, 1, v38
	s_nop 0
	v_cndmask_b32_e64 v48, v38, v48, s[0:1]
	v_fma_f32 v38, -v50, v38, v36
	v_cmp_lt_f32_e64 s[0:1], 0, v38
	s_nop 1
	v_cndmask_b32_e64 v38, v48, v50, s[0:1]
	v_mul_f32_e32 v48, 0x37800000, v38
	v_cndmask_b32_e32 v38, v38, v48, vcc
	v_cmp_class_f32_e32 vcc, v36, v193
	s_nop 1
	v_cndmask_b32_e32 v36, v38, v36, vcc
	v_cmp_ngt_f32_e32 vcc, s23, v33
	s_nop 1
	v_cndmask_b32_e32 v33, 1.0, v36, vcc
	v_mul_f32_e32 v33, v34, v33
	s_waitcnt lgkmcnt(0)
	v_mul_f32_e32 v33, v52, v33
	ds_write_b32 v73, v35 offset:2560
	ds_write_b32 v73, v33 offset:39424
	v_add_f32_e32 v33, v55, v77
	v_mul_f32_e32 v33, 0xbfb8aa3b, v33
	v_exp_f32_e32 v33, v33
	v_add_f32_e32 v34, v39, v76
	v_mul_f32_e32 v34, 0xbfb8aa3b, v34
	v_exp_f32_e32 v34, v34
	v_add_f32_e32 v33, 1.0, v33
	v_rcp_f32_e32 v33, v33
	v_add_f32_e32 v34, 1.0, v34
	v_rcp_f32_e32 v34, v34
	v_mul_f32_e32 v33, v33, v75
	v_mul_f32_e32 v35, 0x3fb8aa3b, v33
	v_add_f32_e32 v33, v33, v33
	v_mul_f32_e32 v36, 0x3fb8aa3b, v33
	v_rndne_f32_e32 v36, v36
	v_fmamk_f32 v38, v36, 0xbf317218, v33
	v_fmac_f32_e32 v38, 0x3102e308, v36
	v_fmamk_f32 v39, v38, 0x395133b1, v192
	v_cmp_eq_f32_e32 vcc, s20, v36
	v_cvt_i32_f32_e32 v36, v36
	v_fmaak_f32 v39, v38, v39, 0x3c0887f9
	v_fmaak_f32 v39, v38, v39, 0x3d2aaa81
	v_fmaak_f32 v39, v38, v39, 0x3e2aaaab
	v_fma_f32 v39, v38, v39, 0.5
	v_ldexp_f32 v36, 1.0, v36
	v_mul_f32_e32 v39, v38, v39
	v_cndmask_b32_e32 v36, v36, v202, vcc
	v_fmac_f32_e32 v38, v38, v39
	v_add_f32_e32 v39, -1.0, v36
	v_fmac_f32_e32 v39, v36, v38
	v_add_f32_e32 v36, v39, v39
	v_cndmask_b32_e32 v36, v39, v36, vcc
	v_cmp_nlt_f32_e32 vcc, s21, v33
	v_exp_f32_e32 v35, v35
	s_nop 0
	v_cndmask_b32_e64 v36, v201, -v36, vcc
	v_cmp_gt_f32_e32 vcc, s22, v36
	v_mul_f32_e32 v38, 0x4f800000, v36
	s_nop 0
	v_cndmask_b32_e32 v36, v36, v38, vcc
	v_sqrt_f32_e32 v38, v36
	s_nop 0
	v_add_u32_e32 v39, -1, v38
	v_fma_f32 v48, -v39, v38, v36
	v_cmp_ge_f32_e64 s[0:1], 0, v48
	v_add_u32_e32 v48, 1, v38
	s_nop 0
	v_cndmask_b32_e64 v39, v38, v39, s[0:1]
	v_fma_f32 v38, -v48, v38, v36
	v_cmp_lt_f32_e64 s[0:1], 0, v38
	s_nop 1
	v_cndmask_b32_e64 v38, v39, v48, s[0:1]
	v_mul_f32_e32 v39, 0x37800000, v38
	v_cndmask_b32_e32 v38, v38, v39, vcc
	v_cmp_class_f32_e32 vcc, v36, v193
	s_nop 1
	v_cndmask_b32_e32 v36, v38, v36, vcc
	ds_read2_b32 v[38:39], v32 offset0:192 offset1:224
	v_cmp_ngt_f32_e32 vcc, s23, v33
	s_nop 1
	v_cndmask_b32_e32 v33, 1.0, v36, vcc
	v_mul_f32_e32 v33, v34, v33
	s_waitcnt lgkmcnt(0)
	v_mul_f32_e32 v32, v38, v33
	ds_write_b32 v73, v35 offset:2816
	ds_write_b32 v73, v32 offset:39680
	v_add_f32_e32 v32, v56, v77
	v_mul_f32_e32 v32, 0xbfb8aa3b, v32
	v_exp_f32_e32 v32, v32
	v_add_f32_e32 v33, v40, v76
	v_mul_f32_e32 v33, 0xbfb8aa3b, v33
	v_exp_f32_e32 v33, v33
	v_add_f32_e32 v32, 1.0, v32
	v_rcp_f32_e32 v32, v32
	v_add_f32_e32 v33, 1.0, v33
	v_rcp_f32_e32 v33, v33
	v_mul_f32_e32 v32, v32, v75
	v_mul_f32_e32 v34, 0x3fb8aa3b, v32
	v_add_f32_e32 v32, v32, v32
	v_mul_f32_e32 v35, 0x3fb8aa3b, v32
	v_rndne_f32_e32 v35, v35
	v_fmamk_f32 v36, v35, 0xbf317218, v32
	v_fmac_f32_e32 v36, 0x3102e308, v35
	v_fmamk_f32 v38, v36, 0x395133b1, v192
	v_cmp_eq_f32_e32 vcc, s20, v35
	v_cvt_i32_f32_e32 v35, v35
	v_fmaak_f32 v38, v36, v38, 0x3c0887f9
	v_fmaak_f32 v38, v36, v38, 0x3d2aaa81
	v_fmaak_f32 v38, v36, v38, 0x3e2aaaab
	v_fma_f32 v38, v36, v38, 0.5
	v_ldexp_f32 v35, 1.0, v35
	v_mul_f32_e32 v38, v36, v38
	v_cndmask_b32_e32 v35, v35, v202, vcc
	v_fmac_f32_e32 v36, v36, v38
	v_add_f32_e32 v38, -1.0, v35
	v_fmac_f32_e32 v38, v35, v36
	v_add_f32_e32 v35, v38, v38
	v_cndmask_b32_e32 v35, v38, v35, vcc
	v_cmp_nlt_f32_e32 vcc, s21, v32
	v_exp_f32_e32 v34, v34
	s_nop 0
	v_cndmask_b32_e64 v35, v201, -v35, vcc
	v_cmp_gt_f32_e32 vcc, s22, v35
	v_mul_f32_e32 v36, 0x4f800000, v35
	s_nop 0
	v_cndmask_b32_e32 v35, v35, v36, vcc
	v_sqrt_f32_e32 v36, v35
	s_nop 0
	v_add_u32_e32 v38, -1, v36
	v_fma_f32 v40, -v38, v36, v35
	v_cmp_ge_f32_e64 s[0:1], 0, v40
	v_add_u32_e32 v40, 1, v36
	s_nop 0
	v_cndmask_b32_e64 v38, v36, v38, s[0:1]
	v_fma_f32 v36, -v40, v36, v35
	v_cmp_lt_f32_e64 s[0:1], 0, v36
	s_nop 1
	v_cndmask_b32_e64 v36, v38, v40, s[0:1]
	v_mul_f32_e32 v38, 0x37800000, v36
	v_cndmask_b32_e32 v36, v36, v38, vcc
	v_cmp_class_f32_e32 vcc, v35, v193
	s_nop 1
	v_cndmask_b32_e32 v35, v36, v35, vcc
	v_cmp_ngt_f32_e32 vcc, s23, v32
	s_nop 1
	v_cndmask_b32_e32 v32, 1.0, v35, vcc
	v_mul_f32_e32 v33, v33, v32
	v_add_u32_e32 v32, 0xa000, v73
	ds_read2_b32 v[54:55], v32 offset1:32
	s_waitcnt lgkmcnt(0)
	v_mul_f32_e32 v33, v54, v33
	ds_write_b32 v73, v34 offset:4096
	ds_write_b32 v73, v33 offset:40960
	v_add_f32_e32 v33, v57, v77
	v_mul_f32_e32 v33, 0xbfb8aa3b, v33
	v_exp_f32_e32 v33, v33
	v_add_f32_e32 v34, v41, v76
	v_mul_f32_e32 v34, 0xbfb8aa3b, v34
	v_exp_f32_e32 v34, v34
	v_add_f32_e32 v33, 1.0, v33
	v_rcp_f32_e32 v33, v33
	v_add_f32_e32 v34, 1.0, v34
	v_rcp_f32_e32 v34, v34
	v_mul_f32_e32 v33, v33, v75
	v_mul_f32_e32 v35, 0x3fb8aa3b, v33
	v_add_f32_e32 v33, v33, v33
	v_mul_f32_e32 v36, 0x3fb8aa3b, v33
	v_rndne_f32_e32 v36, v36
	v_fmamk_f32 v38, v36, 0xbf317218, v33
	v_fmac_f32_e32 v38, 0x3102e308, v36
	v_fmamk_f32 v40, v38, 0x395133b1, v192
	v_cmp_eq_f32_e32 vcc, s20, v36
	v_cvt_i32_f32_e32 v36, v36
	v_fmaak_f32 v40, v38, v40, 0x3c0887f9
	v_fmaak_f32 v40, v38, v40, 0x3d2aaa81
	v_fmaak_f32 v40, v38, v40, 0x3e2aaaab
	v_fma_f32 v40, v38, v40, 0.5
	v_ldexp_f32 v36, 1.0, v36
	v_mul_f32_e32 v40, v38, v40
	v_cndmask_b32_e32 v36, v36, v202, vcc
	v_fmac_f32_e32 v38, v38, v40
	v_add_f32_e32 v40, -1.0, v36
	v_fmac_f32_e32 v40, v36, v38
	v_add_f32_e32 v36, v40, v40
	v_cndmask_b32_e32 v36, v40, v36, vcc
	v_cmp_nlt_f32_e32 vcc, s21, v33
	v_exp_f32_e32 v35, v35
	s_nop 0
	v_cndmask_b32_e64 v36, v201, -v36, vcc
	v_cmp_gt_f32_e32 vcc, s22, v36
	v_mul_f32_e32 v38, 0x4f800000, v36
	s_nop 0
	v_cndmask_b32_e32 v36, v36, v38, vcc
	v_sqrt_f32_e32 v38, v36
	s_nop 0
	v_add_u32_e32 v40, -1, v38
	v_fma_f32 v41, -v40, v38, v36
	v_cmp_ge_f32_e64 s[0:1], 0, v41
	v_add_u32_e32 v41, 1, v38
	s_nop 0
	v_cndmask_b32_e64 v40, v38, v40, s[0:1]
	v_fma_f32 v38, -v41, v38, v36
	v_cmp_lt_f32_e64 s[0:1], 0, v38
	s_nop 1
	v_cndmask_b32_e64 v38, v40, v41, s[0:1]
	v_mul_f32_e32 v40, 0x37800000, v38
	v_cndmask_b32_e32 v38, v38, v40, vcc
	ds_read2_b32 v[40:41], v32 offset0:64 offset1:96
	v_cmp_class_f32_e32 vcc, v36, v193
	s_nop 1
	v_cndmask_b32_e32 v36, v38, v36, vcc
	v_cmp_ngt_f32_e32 vcc, s23, v33
	s_nop 1
	v_cndmask_b32_e32 v33, 1.0, v36, vcc
	v_mul_f32_e32 v33, v34, v33
	s_waitcnt lgkmcnt(0)
	v_mul_f32_e32 v33, v40, v33
	ds_write_b32 v73, v35 offset:4352
	ds_write_b32 v73, v33 offset:41216
	v_add_f32_e32 v33, v58, v77
	v_mul_f32_e32 v33, 0xbfb8aa3b, v33
	v_exp_f32_e32 v33, v33
	v_add_f32_e32 v34, v42, v76
	v_mul_f32_e32 v34, 0xbfb8aa3b, v34
	v_exp_f32_e32 v34, v34
	v_add_f32_e32 v33, 1.0, v33
	v_rcp_f32_e32 v33, v33
	ds_read2_b32 v[56:57], v32 offset0:128 offset1:160
	v_add_f32_e32 v34, 1.0, v34
	v_rcp_f32_e32 v34, v34
	v_mul_f32_e32 v33, v33, v75
	v_mul_f32_e32 v35, 0x3fb8aa3b, v33
	v_add_f32_e32 v33, v33, v33
	v_mul_f32_e32 v36, 0x3fb8aa3b, v33
	v_rndne_f32_e32 v36, v36
	v_fmamk_f32 v38, v36, 0xbf317218, v33
	v_fmac_f32_e32 v38, 0x3102e308, v36
	v_fmamk_f32 v40, v38, 0x395133b1, v192
	v_cmp_eq_f32_e32 vcc, s20, v36
	v_cvt_i32_f32_e32 v36, v36
	v_fmaak_f32 v40, v38, v40, 0x3c0887f9
	v_fmaak_f32 v40, v38, v40, 0x3d2aaa81
	v_fmaak_f32 v40, v38, v40, 0x3e2aaaab
	v_fma_f32 v40, v38, v40, 0.5
	v_ldexp_f32 v36, 1.0, v36
	v_mul_f32_e32 v40, v38, v40
	v_cndmask_b32_e32 v36, v36, v202, vcc
	v_fmac_f32_e32 v38, v38, v40
	v_add_f32_e32 v40, -1.0, v36
	v_fmac_f32_e32 v40, v36, v38
	v_add_f32_e32 v36, v40, v40
	v_cndmask_b32_e32 v36, v40, v36, vcc
	v_cmp_nlt_f32_e32 vcc, s21, v33
	v_exp_f32_e32 v35, v35
	s_nop 0
	v_cndmask_b32_e64 v36, v201, -v36, vcc
	v_cmp_gt_f32_e32 vcc, s22, v36
	v_mul_f32_e32 v38, 0x4f800000, v36
	s_nop 0
	v_cndmask_b32_e32 v36, v36, v38, vcc
	v_sqrt_f32_e32 v38, v36
	s_nop 0
	v_add_u32_e32 v40, -1, v38
	v_fma_f32 v42, -v40, v38, v36
	v_cmp_ge_f32_e64 s[0:1], 0, v42
	v_add_u32_e32 v42, 1, v38
	s_nop 0
	v_cndmask_b32_e64 v40, v38, v40, s[0:1]
	v_fma_f32 v38, -v42, v38, v36
	v_cmp_lt_f32_e64 s[0:1], 0, v38
	s_nop 1
	v_cndmask_b32_e64 v38, v40, v42, s[0:1]
	v_mul_f32_e32 v40, 0x37800000, v38
	v_cndmask_b32_e32 v38, v38, v40, vcc
	v_cmp_class_f32_e32 vcc, v36, v193
	s_nop 1
	v_cndmask_b32_e32 v36, v38, v36, vcc
	v_cmp_ngt_f32_e32 vcc, s23, v33
	s_nop 1
	v_cndmask_b32_e32 v33, 1.0, v36, vcc
	v_mul_f32_e32 v33, v34, v33
	s_waitcnt lgkmcnt(0)
	v_mul_f32_e32 v33, v56, v33
	ds_write_b32 v73, v35 offset:4608
	ds_write_b32 v73, v33 offset:41472
	v_add_f32_e32 v33, v59, v77
	v_mul_f32_e32 v33, 0xbfb8aa3b, v33
	v_exp_f32_e32 v33, v33
	v_add_f32_e32 v34, v43, v76
	v_mul_f32_e32 v34, 0xbfb8aa3b, v34
	v_exp_f32_e32 v34, v34
	v_add_f32_e32 v33, 1.0, v33
	v_rcp_f32_e32 v33, v33
	v_add_f32_e32 v34, 1.0, v34
	v_rcp_f32_e32 v34, v34
	v_mul_f32_e32 v33, v33, v75
	v_mul_f32_e32 v35, 0x3fb8aa3b, v33
	v_add_f32_e32 v33, v33, v33
	v_mul_f32_e32 v36, 0x3fb8aa3b, v33
	v_rndne_f32_e32 v36, v36
	v_fmamk_f32 v38, v36, 0xbf317218, v33
	v_fmac_f32_e32 v38, 0x3102e308, v36
	v_fmamk_f32 v40, v38, 0x395133b1, v192
	v_cmp_eq_f32_e32 vcc, s20, v36
	v_cvt_i32_f32_e32 v36, v36
	v_fmaak_f32 v40, v38, v40, 0x3c0887f9
	v_fmaak_f32 v40, v38, v40, 0x3d2aaa81
	v_fmaak_f32 v40, v38, v40, 0x3e2aaaab
	v_fma_f32 v40, v38, v40, 0.5
	v_ldexp_f32 v36, 1.0, v36
	v_mul_f32_e32 v40, v38, v40
	v_cndmask_b32_e32 v36, v36, v202, vcc
	v_fmac_f32_e32 v38, v38, v40
	v_add_f32_e32 v40, -1.0, v36
	v_fmac_f32_e32 v40, v36, v38
	v_add_f32_e32 v36, v40, v40
	v_cndmask_b32_e32 v36, v40, v36, vcc
	v_cmp_nlt_f32_e32 vcc, s21, v33
	v_exp_f32_e32 v35, v35
	s_nop 0
	v_cndmask_b32_e64 v36, v201, -v36, vcc
	v_cmp_gt_f32_e32 vcc, s22, v36
	v_mul_f32_e32 v38, 0x4f800000, v36
	s_nop 0
	v_cndmask_b32_e32 v36, v36, v38, vcc
	v_sqrt_f32_e32 v38, v36
	s_nop 0
	v_add_u32_e32 v40, -1, v38
	v_fma_f32 v42, -v40, v38, v36
	v_cmp_ge_f32_e64 s[0:1], 0, v42
	v_add_u32_e32 v42, 1, v38
	s_nop 0
	v_cndmask_b32_e64 v40, v38, v40, s[0:1]
	v_fma_f32 v38, -v42, v38, v36
	v_cmp_lt_f32_e64 s[0:1], 0, v38
	s_nop 1
	v_cndmask_b32_e64 v38, v40, v42, s[0:1]
	v_mul_f32_e32 v40, 0x37800000, v38
	ds_read2_b32 v[42:43], v32 offset0:192 offset1:224
	v_cndmask_b32_e32 v38, v38, v40, vcc
	v_cmp_class_f32_e32 vcc, v36, v193
	s_nop 1
	v_cndmask_b32_e32 v36, v38, v36, vcc
	v_cmp_ngt_f32_e32 vcc, s23, v33
	s_nop 1
	v_cndmask_b32_e32 v33, 1.0, v36, vcc
	v_mul_f32_e32 v33, v34, v33
	s_waitcnt lgkmcnt(0)
	v_mul_f32_e32 v32, v42, v33
	ds_write_b32 v73, v35 offset:4864
	ds_write_b32 v73, v32 offset:41728
	v_add_f32_e32 v32, v60, v77
	v_mul_f32_e32 v32, 0xbfb8aa3b, v32
	v_exp_f32_e32 v32, v32
	v_add_f32_e32 v33, v44, v76
	v_mul_f32_e32 v33, 0xbfb8aa3b, v33
	v_exp_f32_e32 v33, v33
	v_add_f32_e32 v32, 1.0, v32
	v_rcp_f32_e32 v32, v32
	v_add_f32_e32 v33, 1.0, v33
	v_rcp_f32_e32 v33, v33
	v_mul_f32_e32 v32, v32, v75
	v_mul_f32_e32 v34, 0x3fb8aa3b, v32
	v_add_f32_e32 v32, v32, v32
	v_mul_f32_e32 v35, 0x3fb8aa3b, v32
	v_rndne_f32_e32 v35, v35
	v_fmamk_f32 v36, v35, 0xbf317218, v32
	v_fmac_f32_e32 v36, 0x3102e308, v35
	v_fmamk_f32 v38, v36, 0x395133b1, v192
	v_cmp_eq_f32_e32 vcc, s20, v35
	v_cvt_i32_f32_e32 v35, v35
	v_fmaak_f32 v38, v36, v38, 0x3c0887f9
	v_fmaak_f32 v38, v36, v38, 0x3d2aaa81
	v_fmaak_f32 v38, v36, v38, 0x3e2aaaab
	v_fma_f32 v38, v36, v38, 0.5
	v_ldexp_f32 v35, 1.0, v35
	v_mul_f32_e32 v38, v36, v38
	v_cndmask_b32_e32 v35, v35, v202, vcc
	v_fmac_f32_e32 v36, v36, v38
	v_add_f32_e32 v38, -1.0, v35
	v_fmac_f32_e32 v38, v35, v36
	v_add_f32_e32 v35, v38, v38
	v_cndmask_b32_e32 v35, v38, v35, vcc
	v_cmp_nlt_f32_e32 vcc, s21, v32
	v_exp_f32_e32 v34, v34
	s_nop 0
	v_cndmask_b32_e64 v35, v201, -v35, vcc
	v_cmp_gt_f32_e32 vcc, s22, v35
	v_mul_f32_e32 v36, 0x4f800000, v35
	s_nop 0
	v_cndmask_b32_e32 v35, v35, v36, vcc
	v_sqrt_f32_e32 v36, v35
	s_nop 0
	v_add_u32_e32 v38, -1, v36
	v_fma_f32 v40, -v38, v36, v35
	v_cmp_ge_f32_e64 s[0:1], 0, v40
	v_add_u32_e32 v40, 1, v36
	s_nop 0
	v_cndmask_b32_e64 v38, v36, v38, s[0:1]
	v_fma_f32 v36, -v40, v36, v35
	v_cmp_lt_f32_e64 s[0:1], 0, v36
	s_nop 1
	v_cndmask_b32_e64 v36, v38, v40, s[0:1]
	v_mul_f32_e32 v38, 0x37800000, v36
	v_cndmask_b32_e32 v36, v36, v38, vcc
	v_cmp_class_f32_e32 vcc, v35, v193
	s_nop 1
	v_cndmask_b32_e32 v35, v36, v35, vcc
	v_cmp_ngt_f32_e32 vcc, s23, v32
	s_nop 1
	v_cndmask_b32_e32 v32, 1.0, v35, vcc
	v_mul_f32_e32 v32, v33, v32
	v_add_u32_e32 v33, 0xa800, v73
	ds_read2_b32 v[58:59], v33 offset1:32
	s_waitcnt lgkmcnt(0)
	v_mul_f32_e32 v32, v58, v32
	ds_write_b32 v73, v34 offset:6144
	ds_write_b32 v73, v32 offset:43008
	v_add_f32_e32 v32, v61, v77
	v_mul_f32_e32 v32, 0xbfb8aa3b, v32
	v_exp_f32_e32 v32, v32
	v_add_f32_e32 v34, v45, v76
	v_mul_f32_e32 v34, 0xbfb8aa3b, v34
	v_exp_f32_e32 v34, v34
	v_add_f32_e32 v32, 1.0, v32
	v_rcp_f32_e32 v32, v32
	ds_read2_b32 v[44:45], v33 offset0:64 offset1:96
	v_add_f32_e32 v34, 1.0, v34
	v_rcp_f32_e32 v34, v34
	v_mul_f32_e32 v32, v32, v75
	v_mul_f32_e32 v35, 0x3fb8aa3b, v32
	v_add_f32_e32 v32, v32, v32
	v_mul_f32_e32 v36, 0x3fb8aa3b, v32
	v_rndne_f32_e32 v36, v36
	v_fmamk_f32 v38, v36, 0xbf317218, v32
	v_fmac_f32_e32 v38, 0x3102e308, v36
	v_fmamk_f32 v40, v38, 0x395133b1, v192
	v_cmp_eq_f32_e32 vcc, s20, v36
	v_cvt_i32_f32_e32 v36, v36
	v_fmaak_f32 v40, v38, v40, 0x3c0887f9
	v_fmaak_f32 v40, v38, v40, 0x3d2aaa81
	v_fmaak_f32 v40, v38, v40, 0x3e2aaaab
	v_fma_f32 v40, v38, v40, 0.5
	v_ldexp_f32 v36, 1.0, v36
	v_mul_f32_e32 v40, v38, v40
	v_cndmask_b32_e32 v36, v36, v202, vcc
	v_fmac_f32_e32 v38, v38, v40
	v_add_f32_e32 v40, -1.0, v36
	v_fmac_f32_e32 v40, v36, v38
	v_add_f32_e32 v36, v40, v40
	v_cndmask_b32_e32 v36, v40, v36, vcc
	v_cmp_nlt_f32_e32 vcc, s21, v32
	v_exp_f32_e32 v35, v35
	s_nop 0
	v_cndmask_b32_e64 v36, v201, -v36, vcc
	v_cmp_gt_f32_e32 vcc, s22, v36
	v_mul_f32_e32 v38, 0x4f800000, v36
	s_nop 0
	v_cndmask_b32_e32 v36, v36, v38, vcc
	v_sqrt_f32_e32 v38, v36
	s_nop 0
	v_add_u32_e32 v40, -1, v38
	v_fma_f32 v42, -v40, v38, v36
	v_cmp_ge_f32_e64 s[0:1], 0, v42
	v_add_u32_e32 v42, 1, v38
	s_nop 0
	v_cndmask_b32_e64 v40, v38, v40, s[0:1]
	v_fma_f32 v38, -v42, v38, v36
	v_cmp_lt_f32_e64 s[0:1], 0, v38
	s_nop 1
	v_cndmask_b32_e64 v38, v40, v42, s[0:1]
	v_mul_f32_e32 v40, 0x37800000, v38
	v_cndmask_b32_e32 v38, v38, v40, vcc
	v_cmp_class_f32_e32 vcc, v36, v193
	s_nop 1
	v_cndmask_b32_e32 v36, v38, v36, vcc
	v_cmp_ngt_f32_e32 vcc, s23, v32
	s_nop 1
	v_cndmask_b32_e32 v32, 1.0, v36, vcc
	v_mul_f32_e32 v32, v34, v32
	s_waitcnt lgkmcnt(0)
	v_mul_f32_e32 v32, v44, v32
	ds_write_b32 v73, v35 offset:6400
	ds_write_b32 v73, v32 offset:43264
	v_add_f32_e32 v32, v62, v77
	v_mul_f32_e32 v32, 0xbfb8aa3b, v32
	v_exp_f32_e32 v32, v32
	v_add_f32_e32 v34, v46, v76
	v_mul_f32_e32 v34, 0xbfb8aa3b, v34
	v_exp_f32_e32 v34, v34
	v_add_f32_e32 v32, 1.0, v32
	v_rcp_f32_e32 v32, v32
	v_add_f32_e32 v34, 1.0, v34
	v_rcp_f32_e32 v34, v34
	v_mul_f32_e32 v32, v32, v75
	v_mul_f32_e32 v35, 0x3fb8aa3b, v32
	v_add_f32_e32 v32, v32, v32
	v_exp_f32_e32 v36, v35
	v_mul_f32_e32 v35, 0x3fb8aa3b, v32
	v_rndne_f32_e32 v35, v35
	v_fmamk_f32 v38, v35, 0xbf317218, v32
	v_fmac_f32_e32 v38, 0x3102e308, v35
	v_fmamk_f32 v40, v38, 0x395133b1, v192
	v_cmp_eq_f32_e32 vcc, s20, v35
	v_cvt_i32_f32_e32 v35, v35
	v_fmaak_f32 v40, v38, v40, 0x3c0887f9
	v_fmaak_f32 v40, v38, v40, 0x3d2aaa81
	v_fmaak_f32 v40, v38, v40, 0x3e2aaaab
	v_fma_f32 v40, v38, v40, 0.5
	v_ldexp_f32 v35, 1.0, v35
	v_mul_f32_e32 v40, v38, v40
	v_cndmask_b32_e32 v35, v35, v202, vcc
	v_fmac_f32_e32 v38, v38, v40
	v_add_f32_e32 v40, -1.0, v35
	v_fmac_f32_e32 v40, v35, v38
	v_add_f32_e32 v35, v40, v40
	v_cndmask_b32_e32 v35, v40, v35, vcc
	v_cmp_nlt_f32_e32 vcc, s21, v32
	s_nop 1
	v_cndmask_b32_e64 v35, v201, -v35, vcc
	v_cmp_gt_f32_e32 vcc, s22, v35
	v_mul_f32_e32 v38, 0x4f800000, v35
	s_nop 0
	v_cndmask_b32_e32 v35, v35, v38, vcc
	v_sqrt_f32_e32 v38, v35
	s_nop 0
	v_add_u32_e32 v40, -1, v38
	v_fma_f32 v42, -v40, v38, v35
	v_cmp_ge_f32_e64 s[0:1], 0, v42
	v_add_u32_e32 v42, 1, v38
	s_nop 0
	v_cndmask_b32_e64 v40, v38, v40, s[0:1]
	v_fma_f32 v38, -v42, v38, v35
	v_cmp_lt_f32_e64 s[0:1], 0, v38
	s_nop 1
	v_cndmask_b32_e64 v38, v40, v42, s[0:1]
	v_mul_f32_e32 v40, 0x37800000, v38
	v_cndmask_b32_e32 v38, v38, v40, vcc
	v_cmp_class_f32_e32 vcc, v35, v193
	s_nop 1
	v_cndmask_b32_e32 v35, v38, v35, vcc
	v_cmp_ngt_f32_e32 vcc, s23, v32
	s_nop 1
	v_cndmask_b32_e32 v32, 1.0, v35, vcc
	v_mul_f32_e32 v32, v34, v32
	ds_read2_b32 v[34:35], v33 offset0:128 offset1:160
	s_waitcnt lgkmcnt(0)
	v_mul_f32_e32 v32, v34, v32
	ds_write_b32 v73, v36 offset:6656
	ds_write_b32 v73, v32 offset:43520
	v_add_f32_e32 v32, v63, v77
	v_mul_f32_e32 v32, 0xbfb8aa3b, v32
	v_exp_f32_e32 v32, v32
	v_add_f32_e32 v34, v47, v76
	v_mul_f32_e32 v34, 0xbfb8aa3b, v34
	v_exp_f32_e32 v34, v34
	v_add_f32_e32 v32, 1.0, v32
	v_rcp_f32_e32 v32, v32
	v_lshlrev_b64 v[46:47], 2, v[96:97]
	v_add_f32_e32 v34, 1.0, v34
	v_rcp_f32_e32 v36, v34
	v_mul_f32_e32 v32, v32, v75
	v_mul_f32_e32 v34, 0x3fb8aa3b, v32
	v_add_f32_e32 v32, v32, v32
	v_mul_f32_e32 v38, 0x3fb8aa3b, v32
	v_rndne_f32_e32 v38, v38
	v_fmamk_f32 v40, v38, 0xbf317218, v32
	v_fmac_f32_e32 v40, 0x3102e308, v38
	v_fmamk_f32 v42, v40, 0x395133b1, v192
	v_cmp_eq_f32_e32 vcc, s20, v38
	v_cvt_i32_f32_e32 v38, v38
	v_fmaak_f32 v42, v40, v42, 0x3c0887f9
	v_fmaak_f32 v42, v40, v42, 0x3d2aaa81
	v_fmaak_f32 v42, v40, v42, 0x3e2aaaab
	v_fma_f32 v42, v40, v42, 0.5
	v_ldexp_f32 v38, 1.0, v38
	v_mul_f32_e32 v42, v40, v42
	v_cndmask_b32_e32 v38, v38, v202, vcc
	v_fmac_f32_e32 v40, v40, v42
	v_add_f32_e32 v42, -1.0, v38
	v_fmac_f32_e32 v42, v38, v40
	v_add_f32_e32 v38, v42, v42
	v_cndmask_b32_e32 v38, v42, v38, vcc
	v_cmp_nlt_f32_e32 vcc, s21, v32
	v_lshl_add_u64 v[60:61], s[18:19], 0, v[46:47]
	v_exp_f32_e32 v34, v34
	v_cndmask_b32_e64 v38, v201, -v38, vcc
	v_cmp_gt_f32_e32 vcc, s22, v38
	v_mul_f32_e32 v40, 0x4f800000, v38
	s_nop 0
	v_cndmask_b32_e32 v38, v38, v40, vcc
	v_sqrt_f32_e32 v40, v38
	s_nop 0
	v_add_u32_e32 v42, -1, v40
	v_fma_f32 v44, -v42, v40, v38
	v_cmp_ge_f32_e64 s[0:1], 0, v44
	v_add_u32_e32 v44, 1, v40
	s_nop 0
	v_cndmask_b32_e64 v42, v40, v42, s[0:1]
	v_fma_f32 v40, -v44, v40, v38
	v_cmp_lt_f32_e64 s[0:1], 0, v40
	s_nop 1
	v_cndmask_b32_e64 v40, v42, v44, s[0:1]
	v_mul_f32_e32 v42, 0x37800000, v40
	v_cndmask_b32_e32 v40, v40, v42, vcc
	v_cmp_class_f32_e32 vcc, v38, v193
	s_nop 1
	v_cndmask_b32_e32 v38, v40, v38, vcc
	v_cmp_ngt_f32_e32 vcc, s23, v32
	s_nop 1
	v_cndmask_b32_e32 v32, 1.0, v38, vcc
	v_mul_f32_e32 v36, v36, v32
	ds_read2_b32 v[32:33], v33 offset0:192 offset1:224
	s_waitcnt lgkmcnt(0)
	v_mul_f32_e32 v32, v32, v36
	ds_write_b32 v73, v32 offset:43776
	v_mov_b32_e32 v32, v226
	s_waitcnt vmcnt(0)
	v_mul_f32_e32 v32, 0xbfb8aa3b, v32
	v_exp_f32_e32 v32, v32
	s_nop 0
	v_add_f32_e32 v36, 1.0, v32
	v_add_f32_e32 v38, -1.0, v36
	v_sub_f32_e32 v40, v38, v36
	v_add_f32_e32 v40, 1.0, v40
	v_sub_f32_e32 v38, v32, v38
	v_add_f32_e32 v38, v38, v40
	v_frexp_mant_f32_e32 v40, v36
	v_cvt_f64_f32_e32 v[60:61], v36
	v_cmp_gt_f32_e32 vcc, s4, v40
	v_frexp_exp_i32_f64_e32 v40, v[60:61]
	s_mul_i32 s4, s11, 0x24000
	v_subbrev_co_u32_e32 v40, vcc, 0, v40, vcc
	v_sub_u32_e32 v42, 0, v40
	v_ldexp_f32 v36, v36, v42
	v_ldexp_f32 v38, v38, v42
	v_add_f32_e32 v42, -1.0, v36
	v_add_f32_e32 v48, 1.0, v36
	v_add_f32_e32 v44, 1.0, v42
	v_add_f32_e32 v50, -1.0, v48
	v_sub_f32_e32 v44, v36, v44
	v_sub_f32_e32 v36, v36, v50
	v_add_f32_e32 v36, v38, v36
	v_add_f32_e32 v44, v38, v44
	v_add_f32_e32 v38, v48, v36
	v_sub_f32_e32 v48, v38, v48
	v_sub_f32_e32 v36, v36, v48
	v_rcp_f32_e32 v48, v38
	v_add_f32_e32 v61, v42, v44
	v_sub_f32_e32 v42, v61, v42
	v_sub_f32_e32 v42, v44, v42
	v_mul_f32_e32 v44, v61, v48
	v_mul_f32_e32 v62, v38, v44
	v_fma_f32 v74, v44, v38, -v62
	v_fmac_f32_e32 v74, v44, v36
	v_add_f32_e32 v60, v62, v74
	v_sub_f32_e32 v63, v61, v60
	v_pk_add_f32 v[76:77], v[60:61], v[62:63] neg_lo:[0,1] neg_hi:[0,1]
	v_mov_b32_e32 v75, v60
	v_pk_add_f32 v[60:61], v[76:77], v[74:75] neg_lo:[0,1] neg_hi:[0,1]
	v_cmp_neq_f32_e32 vcc, s9, v32
	v_add_f32_e32 v42, v42, v61
	v_add_f32_e32 v42, v60, v42
	v_add_f32_e32 v61, v63, v42
	v_mul_f32_e32 v50, v48, v61
	v_mul_f32_e32 v62, v38, v50
	v_fma_f32 v74, v50, v38, -v62
	v_fmac_f32_e32 v74, v50, v36
	v_add_f32_e32 v60, v62, v74
	v_sub_f32_e32 v36, v63, v61
	v_sub_f32_e32 v63, v61, v60
	v_pk_add_f32 v[76:77], v[60:61], v[62:63] neg_lo:[0,1] neg_hi:[0,1]
	v_mov_b32_e32 v75, v60
	v_add_f32_e32 v36, v42, v36
	v_pk_add_f32 v[60:61], v[76:77], v[74:75] neg_lo:[0,1] neg_hi:[0,1]
	v_add_f32_e32 v38, v44, v50
	v_add_f32_e32 v36, v36, v61
	v_add_f32_e32 v36, v60, v36
	v_add_f32_e32 v36, v63, v36
	v_sub_f32_e32 v42, v38, v44
	v_mul_f32_e32 v36, v48, v36
	v_sub_f32_e32 v42, v50, v42
	v_add_f32_e32 v36, v42, v36
	v_add_f32_e32 v42, v38, v36
	v_cvt_f32_i32_e32 v60, v40
	v_mul_f32_e32 v44, v42, v42
	v_fmamk_f32 v48, v44, 0x3e9b6dac, v191
	v_fmaak_f32 v169, v44, v48, 0x3f2aaada
	v_mul_f32_e32 v61, v42, v44
	v_pk_mul_f32 v[74:75], v[60:61], v[168:169]
	v_ldexp_f32 v63, v42, 1
	v_fma_f32 v62, v60, s8, -v74
	v_fmac_f32_e32 v62, 0xb102e308, v60
	v_sub_f32_e32 v38, v42, v38
	v_pk_add_f32 v[60:61], v[74:75], v[62:63]
	v_sub_f32_e32 v36, v36, v38
	v_sub_f32_e32 v38, v61, v63
	v_ldexp_f32 v36, v36, 1
	v_sub_f32_e32 v38, v75, v38
	v_add_f32_e32 v77, v36, v38
	v_mov_b32_e32 v76, v74
	v_pk_add_f32 v[74:75], v[60:61], v[74:75] neg_lo:[0,1] neg_hi:[0,1]
	v_pk_add_f32 v[78:79], v[60:61], v[76:77]
	v_mov_b32_e32 v63, v60
	v_mov_b32_e32 v75, v79
	v_pk_add_f32 v[80:81], v[62:63], v[74:75] neg_lo:[0,1] neg_hi:[0,1]
	v_pk_add_f32 v[62:63], v[62:63], v[74:75]
	v_mov_b32_e32 v76, v77
	v_pk_add_f32 v[74:75], v[62:63], v[60:61] op_sel:[1,0] op_sel_hi:[0,1] neg_lo:[0,1] neg_hi:[0,1]
	v_pk_add_f32 v[82:83], v[78:79], v[74:75] op_sel_hi:[1,0] neg_lo:[0,1] neg_hi:[0,1]
	v_mov_b32_e32 v78, v79
	v_mov_b32_e32 v79, v63
	v_pk_mov_b32 v[74:75], v[60:61], v[74:75] op_sel:[1,0]
	v_mov_b32_e32 v77, v60
	v_pk_add_f32 v[74:75], v[78:79], v[74:75] neg_lo:[0,1] neg_hi:[0,1]
	v_mov_b32_e32 v82, v80
	v_pk_add_f32 v[60:61], v[76:77], v[74:75] neg_lo:[0,1] neg_hi:[0,1]
	v_mov_b32_e32 v81, v63
	v_pk_add_f32 v[74:75], v[82:83], v[60:61]
	v_pk_add_f32 v[76:77], v[74:75], v[74:75] op_sel:[0,1] op_sel_hi:[1,0]
	v_pk_add_f32 v[62:63], v[62:63], v[76:77] op_sel:[1,0] op_sel_hi:[0,1]
	v_mov_b32_e32 v75, v62
	v_pk_add_f32 v[78:79], v[74:75], v[80:81] neg_lo:[0,1] neg_hi:[0,1]
	v_mov_b32_e32 v61, v76
	v_sub_f32_e32 v36, v74, v78
	v_pk_add_f32 v[60:61], v[60:61], v[78:79] neg_lo:[0,1] neg_hi:[0,1]
	v_sub_f32_e32 v36, v80, v36
	v_add_f32_e32 v36, v60, v36
	v_add_f32_e32 v36, v36, v61
	v_add_f32_e32 v36, v62, v36
	v_cndmask_b32_e32 v36, v199, v36, vcc
	v_cmp_ngt_f32_e32 vcc, -1.0, v32
	v_lshl_add_u64 v[60:61], s[52:53], 0, v[46:47]
	v_lshl_add_u64 v[46:47], s[16:17], 0, v[46:47]
	v_cndmask_b32_e32 v36, v200, v36, vcc
	v_cmp_neq_f32_e32 vcc, -1.0, v32
	v_mov_b32_e32 v38, v227
	s_waitcnt vmcnt(0)
	v_add_f32_e32 v0, v0, v38
	v_cndmask_b32_e32 v36, v201, v36, vcc
	v_cmp_lt_f32_e64 vcc, |v32|, s10
	v_mul_f32_e32 v0, 0xbfb8aa3b, v0
	v_exp_f32_e32 v0, v0
	v_cndmask_b32_e32 v32, v36, v32, vcc
	v_mov_b32_e32 v36, v228
	v_mul_f32_e32 v32, 0xc1000000, v32
	v_add_f32_e32 v0, 1.0, v0
	v_rcp_f32_e32 v0, v0
	v_add_f32_e32 v1, v1, v38
	v_mul_f32_e32 v1, 0xbfb8aa3b, v1
	v_exp_f32_e32 v1, v1
	s_waitcnt vmcnt(0)
	v_add_f32_e32 v16, v16, v36
	v_mul_f32_e32 v16, 0xbfb8aa3b, v16
	v_exp_f32_e32 v16, v16
	v_add_f32_e32 v1, 1.0, v1
	v_rcp_f32_e32 v1, v1
	v_add_f32_e32 v16, 1.0, v16
	v_rcp_f32_e32 v16, v16
	s_nop 0
	v_mul_f32_e32 v16, v16, v32
	v_mul_f32_e32 v40, 0x3fb8aa3b, v16
	v_add_f32_e32 v16, v16, v16
	v_mul_f32_e32 v42, 0x3fb8aa3b, v16
	v_rndne_f32_e32 v42, v42
	v_fmamk_f32 v44, v42, 0xbf317218, v16
	v_fmac_f32_e32 v44, 0x3102e308, v42
	v_fmamk_f32 v46, v44, 0x395133b1, v192
	v_cmp_eq_f32_e32 vcc, s20, v42
	v_cvt_i32_f32_e32 v42, v42
	v_fmaak_f32 v46, v44, v46, 0x3c0887f9
	v_fmaak_f32 v46, v44, v46, 0x3d2aaa81
	v_fmaak_f32 v46, v44, v46, 0x3e2aaaab
	v_fma_f32 v46, v44, v46, 0.5
	v_ldexp_f32 v42, 1.0, v42
	v_mul_f32_e32 v46, v44, v46
	v_cndmask_b32_e32 v42, v42, v202, vcc
	v_fmac_f32_e32 v44, v44, v46
	v_add_f32_e32 v46, -1.0, v42
	v_fmac_f32_e32 v46, v42, v44
	v_add_f32_e32 v42, v46, v46
	v_cndmask_b32_e32 v42, v46, v42, vcc
	v_cmp_nlt_f32_e32 vcc, s21, v16
	v_exp_f32_e32 v40, v40
	s_nop 0
	v_cndmask_b32_e64 v42, v201, -v42, vcc
	v_cmp_gt_f32_e32 vcc, s22, v42
	v_mul_f32_e32 v44, 0x4f800000, v42
	s_nop 0
	v_cndmask_b32_e32 v42, v42, v44, vcc
	v_sqrt_f32_e32 v44, v42
	s_nop 0
	v_add_u32_e32 v46, -1, v44
	v_fma_f32 v47, -v46, v44, v42
	v_cmp_ge_f32_e64 s[0:1], 0, v47
	v_add_u32_e32 v47, 1, v44
	s_nop 0
	v_cndmask_b32_e64 v46, v44, v46, s[0:1]
	v_fma_f32 v44, -v47, v44, v42
	v_cmp_lt_f32_e64 s[0:1], 0, v44
	s_nop 1
	v_cndmask_b32_e64 v44, v46, v47, s[0:1]
	v_mul_f32_e32 v46, 0x37800000, v44
	v_cndmask_b32_e32 v44, v44, v46, vcc
	v_cmp_class_f32_e32 vcc, v42, v193
	s_nop 1
	v_cndmask_b32_e32 v42, v44, v42, vcc
	v_cmp_ngt_f32_e32 vcc, s23, v16
	s_nop 1
	v_cndmask_b32_e32 v16, 1.0, v42, vcc
	v_mul_f32_e32 v0, v0, v16
	v_mul_f32_e32 v0, v67, v0
	ds_write_b32 v73, v40 offset:128
	ds_write_b32 v73, v0 offset:36992
	v_add_f32_e32 v0, v17, v36
	v_mul_f32_e32 v0, 0xbfb8aa3b, v0
	v_exp_f32_e32 v0, v0
	s_nop 0
	v_add_f32_e32 v0, 1.0, v0
	v_rcp_f32_e32 v0, v0
	s_nop 0
	v_mul_f32_e32 v0, v0, v32
	v_mul_f32_e32 v16, 0x3fb8aa3b, v0
	v_add_f32_e32 v0, v0, v0
	v_mul_f32_e32 v17, 0x3fb8aa3b, v0
	v_rndne_f32_e32 v17, v17
	v_fmamk_f32 v40, v17, 0xbf317218, v0
	v_fmac_f32_e32 v40, 0x3102e308, v17
	v_fmamk_f32 v42, v40, 0x395133b1, v192
	v_cmp_eq_f32_e32 vcc, s20, v17
	v_cvt_i32_f32_e32 v17, v17
	v_fmaak_f32 v42, v40, v42, 0x3c0887f9
	v_fmaak_f32 v42, v40, v42, 0x3d2aaa81
	v_fmaak_f32 v42, v40, v42, 0x3e2aaaab
	v_fma_f32 v42, v40, v42, 0.5
	v_ldexp_f32 v17, 1.0, v17
	v_mul_f32_e32 v42, v40, v42
	v_cndmask_b32_e32 v17, v17, v202, vcc
	v_fmac_f32_e32 v40, v40, v42
	v_add_f32_e32 v42, -1.0, v17
	v_fmac_f32_e32 v42, v17, v40
	v_add_f32_e32 v17, v42, v42
	v_cndmask_b32_e32 v17, v42, v17, vcc
	v_cmp_nlt_f32_e32 vcc, s21, v0
	v_exp_f32_e32 v16, v16
	s_nop 0
	v_cndmask_b32_e64 v17, v201, -v17, vcc
	v_cmp_gt_f32_e32 vcc, s22, v17
	v_mul_f32_e32 v40, 0x4f800000, v17
	s_nop 0
	v_cndmask_b32_e32 v17, v17, v40, vcc
	v_sqrt_f32_e32 v40, v17
	s_nop 0
	v_add_u32_e32 v42, -1, v40
	v_fma_f32 v44, -v42, v40, v17
	v_cmp_ge_f32_e64 s[0:1], 0, v44
	v_add_u32_e32 v44, 1, v40
	s_nop 0
	v_cndmask_b32_e64 v42, v40, v42, s[0:1]
	v_fma_f32 v40, -v44, v40, v17
	v_cmp_lt_f32_e64 s[0:1], 0, v40
	s_nop 1
	v_cndmask_b32_e64 v40, v42, v44, s[0:1]
	v_mul_f32_e32 v42, 0x37800000, v40
	v_cndmask_b32_e32 v40, v40, v42, vcc
	v_cmp_class_f32_e32 vcc, v17, v193
	s_nop 1
	v_cndmask_b32_e32 v17, v40, v17, vcc
	v_cmp_ngt_f32_e32 vcc, s23, v0
	s_nop 1
	v_cndmask_b32_e32 v0, 1.0, v17, vcc
	v_mul_f32_e32 v0, v1, v0
	v_mul_f32_e32 v0, v49, v0
	ds_write_b32 v73, v16 offset:384
	ds_write_b32 v73, v0 offset:37248
	v_add_f32_e32 v0, v18, v36
	v_mul_f32_e32 v0, 0xbfb8aa3b, v0
	v_exp_f32_e32 v0, v0
	v_add_f32_e32 v1, v2, v38
	v_mul_f32_e32 v1, 0xbfb8aa3b, v1
	v_exp_f32_e32 v1, v1
	v_add_f32_e32 v0, 1.0, v0
	v_rcp_f32_e32 v0, v0
	v_add_f32_e32 v1, 1.0, v1
	v_rcp_f32_e32 v1, v1
	v_mul_f32_e32 v0, v0, v32
	v_mul_f32_e32 v2, 0x3fb8aa3b, v0
	v_add_f32_e32 v0, v0, v0
	v_mul_f32_e32 v16, 0x3fb8aa3b, v0
	v_rndne_f32_e32 v16, v16
	v_fmamk_f32 v17, v16, 0xbf317218, v0
	v_fmac_f32_e32 v17, 0x3102e308, v16
	v_fmamk_f32 v18, v17, 0x395133b1, v192
	v_cmp_eq_f32_e32 vcc, s20, v16
	v_cvt_i32_f32_e32 v16, v16
	v_fmaak_f32 v18, v17, v18, 0x3c0887f9
	v_fmaak_f32 v18, v17, v18, 0x3d2aaa81
	v_fmaak_f32 v18, v17, v18, 0x3e2aaaab
	v_fma_f32 v18, v17, v18, 0.5
	v_ldexp_f32 v16, 1.0, v16
	v_mul_f32_e32 v18, v17, v18
	v_cndmask_b32_e32 v16, v16, v202, vcc
	v_fmac_f32_e32 v17, v17, v18
	v_add_f32_e32 v18, -1.0, v16
	v_fmac_f32_e32 v18, v16, v17
	v_add_f32_e32 v16, v18, v18
	v_cndmask_b32_e32 v16, v18, v16, vcc
	v_cmp_nlt_f32_e32 vcc, s21, v0
	v_exp_f32_e32 v2, v2
	s_nop 0
	v_cndmask_b32_e64 v16, v201, -v16, vcc
	v_cmp_gt_f32_e32 vcc, s22, v16
	v_mul_f32_e32 v17, 0x4f800000, v16
	s_nop 0
	v_cndmask_b32_e32 v16, v16, v17, vcc
	v_sqrt_f32_e32 v17, v16
	s_nop 0
	v_add_u32_e32 v18, -1, v17
	v_fma_f32 v40, -v18, v17, v16
	v_cmp_ge_f32_e64 s[0:1], 0, v40
	v_add_u32_e32 v40, 1, v17
	s_nop 0
	v_cndmask_b32_e64 v18, v17, v18, s[0:1]
	v_fma_f32 v17, -v40, v17, v16
	v_cmp_lt_f32_e64 s[0:1], 0, v17
	s_nop 1
	v_cndmask_b32_e64 v17, v18, v40, s[0:1]
	v_mul_f32_e32 v18, 0x37800000, v17
	v_cndmask_b32_e32 v17, v17, v18, vcc
	v_cmp_class_f32_e32 vcc, v16, v193
	s_nop 1
	v_cndmask_b32_e32 v16, v17, v16, vcc
	v_cmp_ngt_f32_e32 vcc, s23, v0
	s_nop 1
	v_cndmask_b32_e32 v0, 1.0, v16, vcc
	v_mul_f32_e32 v0, v1, v0
	v_mul_f32_e32 v0, v69, v0
	ds_write_b32 v73, v2 offset:640
	ds_write_b32 v73, v0 offset:37504
	v_add_f32_e32 v0, v19, v36
	v_mul_f32_e32 v0, 0xbfb8aa3b, v0
	v_exp_f32_e32 v0, v0
	v_add_f32_e32 v1, v3, v38
	v_mul_f32_e32 v1, 0xbfb8aa3b, v1
	v_exp_f32_e32 v1, v1
	v_add_f32_e32 v0, 1.0, v0
	v_rcp_f32_e32 v0, v0
	v_add_f32_e32 v1, 1.0, v1
	v_rcp_f32_e32 v1, v1
	v_mul_f32_e32 v0, v0, v32
	v_mul_f32_e32 v2, 0x3fb8aa3b, v0
	v_add_f32_e32 v0, v0, v0
	v_mul_f32_e32 v3, 0x3fb8aa3b, v0
	v_rndne_f32_e32 v3, v3
	v_fmamk_f32 v16, v3, 0xbf317218, v0
	v_fmac_f32_e32 v16, 0x3102e308, v3
	v_fmamk_f32 v17, v16, 0x395133b1, v192
	v_cmp_eq_f32_e32 vcc, s20, v3
	v_cvt_i32_f32_e32 v3, v3
	v_fmaak_f32 v17, v16, v17, 0x3c0887f9
	v_fmaak_f32 v17, v16, v17, 0x3d2aaa81
	v_fmaak_f32 v17, v16, v17, 0x3e2aaaab
	v_fma_f32 v17, v16, v17, 0.5
	v_ldexp_f32 v3, 1.0, v3
	v_mul_f32_e32 v17, v16, v17
	v_cndmask_b32_e32 v3, v3, v202, vcc
	v_fmac_f32_e32 v16, v16, v17
	v_add_f32_e32 v17, -1.0, v3
	v_fmac_f32_e32 v17, v3, v16
	v_add_f32_e32 v3, v17, v17
	v_cndmask_b32_e32 v3, v17, v3, vcc
	v_cmp_nlt_f32_e32 vcc, s21, v0
	v_exp_f32_e32 v2, v2
	s_nop 0
	v_cndmask_b32_e64 v3, v201, -v3, vcc
	v_cmp_gt_f32_e32 vcc, s22, v3
	v_mul_f32_e32 v16, 0x4f800000, v3
	s_nop 0
	v_cndmask_b32_e32 v3, v3, v16, vcc
	v_sqrt_f32_e32 v16, v3
	s_nop 0
	v_add_u32_e32 v17, -1, v16
	v_fma_f32 v18, -v17, v16, v3
	v_cmp_ge_f32_e64 s[0:1], 0, v18
	v_add_u32_e32 v18, 1, v16
	s_nop 0
	v_cndmask_b32_e64 v17, v16, v17, s[0:1]
	v_fma_f32 v16, -v18, v16, v3
	v_cmp_lt_f32_e64 s[0:1], 0, v16
	s_nop 1
	v_cndmask_b32_e64 v16, v17, v18, s[0:1]
	v_mul_f32_e32 v17, 0x37800000, v16
	v_cndmask_b32_e32 v16, v16, v17, vcc
	v_cmp_class_f32_e32 vcc, v3, v193
	s_nop 1
	v_cndmask_b32_e32 v3, v16, v3, vcc
	v_cmp_ngt_f32_e32 vcc, s23, v0
	s_nop 1
	v_cndmask_b32_e32 v0, 1.0, v3, vcc
	v_mul_f32_e32 v0, v1, v0
	v_mul_f32_e32 v0, v51, v0
	ds_write_b32 v73, v2 offset:896
	ds_write_b32 v73, v0 offset:37760
	v_add_f32_e32 v0, v20, v36
	v_mul_f32_e32 v0, 0xbfb8aa3b, v0
	v_exp_f32_e32 v0, v0
	v_add_f32_e32 v1, v4, v38
	v_mul_f32_e32 v1, 0xbfb8aa3b, v1
	v_exp_f32_e32 v1, v1
	v_add_f32_e32 v0, 1.0, v0
	v_rcp_f32_e32 v0, v0
	v_add_f32_e32 v1, 1.0, v1
	v_rcp_f32_e32 v1, v1
	v_mul_f32_e32 v0, v0, v32
	v_mul_f32_e32 v2, 0x3fb8aa3b, v0
	v_add_f32_e32 v0, v0, v0
	v_mul_f32_e32 v3, 0x3fb8aa3b, v0
	v_rndne_f32_e32 v3, v3
	v_fmamk_f32 v4, v3, 0xbf317218, v0
	v_fmac_f32_e32 v4, 0x3102e308, v3
	v_fmamk_f32 v16, v4, 0x395133b1, v192
	v_cmp_eq_f32_e32 vcc, s20, v3
	v_cvt_i32_f32_e32 v3, v3
	v_fmaak_f32 v16, v4, v16, 0x3c0887f9
	v_fmaak_f32 v16, v4, v16, 0x3d2aaa81
	v_fmaak_f32 v16, v4, v16, 0x3e2aaaab
	v_fma_f32 v16, v4, v16, 0.5
	v_ldexp_f32 v3, 1.0, v3
	v_mul_f32_e32 v16, v4, v16
	v_cndmask_b32_e32 v3, v3, v202, vcc
	v_fmac_f32_e32 v4, v4, v16
	v_add_f32_e32 v16, -1.0, v3
	v_fmac_f32_e32 v16, v3, v4
	v_add_f32_e32 v3, v16, v16
	v_cndmask_b32_e32 v3, v16, v3, vcc
	v_cmp_nlt_f32_e32 vcc, s21, v0
	v_exp_f32_e32 v2, v2
	s_nop 0
	v_cndmask_b32_e64 v3, v201, -v3, vcc
	v_cmp_gt_f32_e32 vcc, s22, v3
	v_mul_f32_e32 v4, 0x4f800000, v3
	s_nop 0
	v_cndmask_b32_e32 v3, v3, v4, vcc
	v_sqrt_f32_e32 v4, v3
	s_nop 0
	v_add_u32_e32 v16, -1, v4
	v_fma_f32 v17, -v16, v4, v3
	v_cmp_ge_f32_e64 s[0:1], 0, v17
	v_add_u32_e32 v17, 1, v4
	s_nop 0
	v_cndmask_b32_e64 v16, v4, v16, s[0:1]
	v_fma_f32 v4, -v17, v4, v3
	v_cmp_lt_f32_e64 s[0:1], 0, v4
	s_nop 1
	v_cndmask_b32_e64 v4, v16, v17, s[0:1]
	v_mul_f32_e32 v16, 0x37800000, v4
	v_cndmask_b32_e32 v4, v4, v16, vcc
	v_cmp_class_f32_e32 vcc, v3, v193
	s_nop 1
	v_cndmask_b32_e32 v3, v4, v3, vcc
	v_cmp_ngt_f32_e32 vcc, s23, v0
	s_nop 1
	v_cndmask_b32_e32 v0, 1.0, v3, vcc
	v_mul_f32_e32 v0, v1, v0
	v_mul_f32_e32 v0, v71, v0
	ds_write_b32 v73, v2 offset:2176
	ds_write_b32 v73, v0 offset:39040
	v_add_f32_e32 v0, v21, v36
	v_mul_f32_e32 v0, 0xbfb8aa3b, v0
	v_exp_f32_e32 v0, v0
	v_add_f32_e32 v1, v5, v38
	v_mul_f32_e32 v1, 0xbfb8aa3b, v1
	v_exp_f32_e32 v1, v1
	v_add_f32_e32 v0, 1.0, v0
	v_rcp_f32_e32 v0, v0
	v_add_f32_e32 v1, 1.0, v1
	v_rcp_f32_e32 v1, v1
	v_mul_f32_e32 v0, v0, v32
	v_mul_f32_e32 v2, 0x3fb8aa3b, v0
	v_add_f32_e32 v0, v0, v0
	v_mul_f32_e32 v3, 0x3fb8aa3b, v0
	v_rndne_f32_e32 v3, v3
	v_fmamk_f32 v4, v3, 0xbf317218, v0
	v_fmac_f32_e32 v4, 0x3102e308, v3
	v_fmamk_f32 v5, v4, 0x395133b1, v192
	v_cmp_eq_f32_e32 vcc, s20, v3
	v_cvt_i32_f32_e32 v3, v3
	v_fmaak_f32 v5, v4, v5, 0x3c0887f9
	v_fmaak_f32 v5, v4, v5, 0x3d2aaa81
	v_fmaak_f32 v5, v4, v5, 0x3e2aaaab
	v_fma_f32 v5, v4, v5, 0.5
	v_ldexp_f32 v3, 1.0, v3
	v_mul_f32_e32 v5, v4, v5
	v_cndmask_b32_e32 v3, v3, v202, vcc
	v_fmac_f32_e32 v4, v4, v5
	v_add_f32_e32 v5, -1.0, v3
	v_fmac_f32_e32 v5, v3, v4
	v_add_f32_e32 v3, v5, v5
	v_cndmask_b32_e32 v3, v5, v3, vcc
	v_cmp_nlt_f32_e32 vcc, s21, v0
	v_exp_f32_e32 v2, v2
	s_nop 0
	v_cndmask_b32_e64 v3, v201, -v3, vcc
	v_cmp_gt_f32_e32 vcc, s22, v3
	v_mul_f32_e32 v4, 0x4f800000, v3
	s_nop 0
	v_cndmask_b32_e32 v3, v3, v4, vcc
	v_sqrt_f32_e32 v4, v3
	s_nop 0
	v_add_u32_e32 v5, -1, v4
	v_fma_f32 v16, -v5, v4, v3
	v_cmp_ge_f32_e64 s[0:1], 0, v16
	v_add_u32_e32 v16, 1, v4
	s_nop 0
	v_cndmask_b32_e64 v5, v4, v5, s[0:1]
	v_fma_f32 v4, -v16, v4, v3
	v_cmp_lt_f32_e64 s[0:1], 0, v4
	s_nop 1
	v_cndmask_b32_e64 v4, v5, v16, s[0:1]
	v_mul_f32_e32 v5, 0x37800000, v4
	v_cndmask_b32_e32 v4, v4, v5, vcc
	v_cmp_class_f32_e32 vcc, v3, v193
	s_nop 1
	v_cndmask_b32_e32 v3, v4, v3, vcc
	v_cmp_ngt_f32_e32 vcc, s23, v0
	s_nop 1
	v_cndmask_b32_e32 v0, 1.0, v3, vcc
	v_mul_f32_e32 v0, v1, v0
	v_mul_f32_e32 v0, v37, v0
	ds_write_b32 v73, v2 offset:2432
	ds_write_b32 v73, v0 offset:39296
	v_add_f32_e32 v0, v22, v36
	v_mul_f32_e32 v0, 0xbfb8aa3b, v0
	v_exp_f32_e32 v0, v0
	v_add_f32_e32 v1, v6, v38
	v_mul_f32_e32 v1, 0xbfb8aa3b, v1
	v_exp_f32_e32 v1, v1
	v_add_f32_e32 v0, 1.0, v0
	v_rcp_f32_e32 v0, v0
	v_add_f32_e32 v1, 1.0, v1
	v_rcp_f32_e32 v1, v1
	v_mul_f32_e32 v0, v0, v32
	v_mul_f32_e32 v2, 0x3fb8aa3b, v0
	v_add_f32_e32 v0, v0, v0
	v_mul_f32_e32 v3, 0x3fb8aa3b, v0
	v_rndne_f32_e32 v3, v3
	v_fmamk_f32 v4, v3, 0xbf317218, v0
	v_fmac_f32_e32 v4, 0x3102e308, v3
	v_fmamk_f32 v5, v4, 0x395133b1, v192
	v_cmp_eq_f32_e32 vcc, s20, v3
	v_cvt_i32_f32_e32 v3, v3
	v_fmaak_f32 v5, v4, v5, 0x3c0887f9
	v_fmaak_f32 v5, v4, v5, 0x3d2aaa81
	v_fmaak_f32 v5, v4, v5, 0x3e2aaaab
	v_fma_f32 v5, v4, v5, 0.5
	v_ldexp_f32 v3, 1.0, v3
	v_mul_f32_e32 v5, v4, v5
	v_cndmask_b32_e32 v3, v3, v202, vcc
	v_fmac_f32_e32 v4, v4, v5
	v_add_f32_e32 v5, -1.0, v3
	v_fmac_f32_e32 v5, v3, v4
	v_add_f32_e32 v3, v5, v5
	v_cndmask_b32_e32 v3, v5, v3, vcc
	v_cmp_nlt_f32_e32 vcc, s21, v0
	v_exp_f32_e32 v2, v2
	s_nop 0
	v_cndmask_b32_e64 v3, v201, -v3, vcc
	v_cmp_gt_f32_e32 vcc, s22, v3
	v_mul_f32_e32 v4, 0x4f800000, v3
	s_nop 0
	v_cndmask_b32_e32 v3, v3, v4, vcc
	v_sqrt_f32_e32 v4, v3
	s_nop 0
	v_add_u32_e32 v5, -1, v4
	v_fma_f32 v6, -v5, v4, v3
	v_cmp_ge_f32_e64 s[0:1], 0, v6
	v_add_u32_e32 v6, 1, v4
	s_nop 0
	v_cndmask_b32_e64 v5, v4, v5, s[0:1]
	v_fma_f32 v4, -v6, v4, v3
	v_cmp_lt_f32_e64 s[0:1], 0, v4
	s_nop 1
	v_cndmask_b32_e64 v4, v5, v6, s[0:1]
	v_mul_f32_e32 v5, 0x37800000, v4
	v_cndmask_b32_e32 v4, v4, v5, vcc
	v_cmp_class_f32_e32 vcc, v3, v193
	s_nop 1
	v_cndmask_b32_e32 v3, v4, v3, vcc
	v_cmp_ngt_f32_e32 vcc, s23, v0
	s_nop 1
	v_cndmask_b32_e32 v0, 1.0, v3, vcc
	v_mul_f32_e32 v0, v1, v0
	v_mul_f32_e32 v0, v53, v0
	ds_write_b32 v73, v2 offset:2688
	ds_write_b32 v73, v0 offset:39552
	v_add_f32_e32 v0, v23, v36
	v_mul_f32_e32 v0, 0xbfb8aa3b, v0
	v_exp_f32_e32 v0, v0
	v_add_f32_e32 v1, v7, v38
	v_mul_f32_e32 v1, 0xbfb8aa3b, v1
	v_exp_f32_e32 v1, v1
	v_add_f32_e32 v0, 1.0, v0
	v_rcp_f32_e32 v0, v0
	v_add_f32_e32 v1, 1.0, v1
	v_rcp_f32_e32 v1, v1
	v_mul_f32_e32 v0, v0, v32
	v_mul_f32_e32 v2, 0x3fb8aa3b, v0
	v_add_f32_e32 v0, v0, v0
	v_mul_f32_e32 v3, 0x3fb8aa3b, v0
	v_rndne_f32_e32 v3, v3
	v_fmamk_f32 v4, v3, 0xbf317218, v0
	v_fmac_f32_e32 v4, 0x3102e308, v3
	v_fmamk_f32 v5, v4, 0x395133b1, v192
	v_cmp_eq_f32_e32 vcc, s20, v3
	v_cvt_i32_f32_e32 v3, v3
	v_fmaak_f32 v5, v4, v5, 0x3c0887f9
	v_fmaak_f32 v5, v4, v5, 0x3d2aaa81
	v_fmaak_f32 v5, v4, v5, 0x3e2aaaab
	v_fma_f32 v5, v4, v5, 0.5
	v_ldexp_f32 v3, 1.0, v3
	v_mul_f32_e32 v5, v4, v5
	v_cndmask_b32_e32 v3, v3, v202, vcc
	v_fmac_f32_e32 v4, v4, v5
	v_add_f32_e32 v5, -1.0, v3
	v_fmac_f32_e32 v5, v3, v4
	v_add_f32_e32 v3, v5, v5
	v_cndmask_b32_e32 v3, v5, v3, vcc
	v_cmp_nlt_f32_e32 vcc, s21, v0
	v_exp_f32_e32 v2, v2
	s_nop 0
	v_cndmask_b32_e64 v3, v201, -v3, vcc
	v_cmp_gt_f32_e32 vcc, s22, v3
	v_mul_f32_e32 v4, 0x4f800000, v3
	s_nop 0
	v_cndmask_b32_e32 v3, v3, v4, vcc
	v_sqrt_f32_e32 v4, v3
	s_nop 0
	v_add_u32_e32 v5, -1, v4
	v_fma_f32 v6, -v5, v4, v3
	v_cmp_ge_f32_e64 s[0:1], 0, v6
	v_add_u32_e32 v6, 1, v4
	s_nop 0
	v_cndmask_b32_e64 v5, v4, v5, s[0:1]
	v_fma_f32 v4, -v6, v4, v3
	v_cmp_lt_f32_e64 s[0:1], 0, v4
	s_nop 1
	v_cndmask_b32_e64 v4, v5, v6, s[0:1]
	v_mul_f32_e32 v5, 0x37800000, v4
	v_cndmask_b32_e32 v4, v4, v5, vcc
	v_cmp_class_f32_e32 vcc, v3, v193
	s_nop 1
	v_cndmask_b32_e32 v3, v4, v3, vcc
	v_cmp_ngt_f32_e32 vcc, s23, v0
	s_nop 1
	v_cndmask_b32_e32 v0, 1.0, v3, vcc
	v_mul_f32_e32 v0, v1, v0
	v_mul_f32_e32 v0, v39, v0
	ds_write_b32 v73, v2 offset:2944
	ds_write_b32 v73, v0 offset:39808
	v_add_f32_e32 v0, v24, v36
	v_mul_f32_e32 v0, 0xbfb8aa3b, v0
	v_exp_f32_e32 v0, v0
	v_add_f32_e32 v1, v8, v38
	v_mul_f32_e32 v1, 0xbfb8aa3b, v1
	v_exp_f32_e32 v1, v1
	v_add_f32_e32 v0, 1.0, v0
	v_rcp_f32_e32 v0, v0
	v_add_f32_e32 v1, 1.0, v1
	v_rcp_f32_e32 v1, v1
	v_mul_f32_e32 v0, v0, v32
	v_mul_f32_e32 v2, 0x3fb8aa3b, v0
	v_add_f32_e32 v0, v0, v0
	v_mul_f32_e32 v3, 0x3fb8aa3b, v0
	v_rndne_f32_e32 v3, v3
	v_fmamk_f32 v4, v3, 0xbf317218, v0
	v_fmac_f32_e32 v4, 0x3102e308, v3
	v_fmamk_f32 v5, v4, 0x395133b1, v192
	v_cmp_eq_f32_e32 vcc, s20, v3
	v_cvt_i32_f32_e32 v3, v3
	v_fmaak_f32 v5, v4, v5, 0x3c0887f9
	v_fmaak_f32 v5, v4, v5, 0x3d2aaa81
	v_fmaak_f32 v5, v4, v5, 0x3e2aaaab
	v_fma_f32 v5, v4, v5, 0.5
	v_ldexp_f32 v3, 1.0, v3
	v_mul_f32_e32 v5, v4, v5
	v_cndmask_b32_e32 v3, v3, v202, vcc
	v_fmac_f32_e32 v4, v4, v5
	v_add_f32_e32 v5, -1.0, v3
	v_fmac_f32_e32 v5, v3, v4
	v_add_f32_e32 v3, v5, v5
	v_cndmask_b32_e32 v3, v5, v3, vcc
	v_cmp_nlt_f32_e32 vcc, s21, v0
	v_exp_f32_e32 v2, v2
	s_nop 0
	v_cndmask_b32_e64 v3, v201, -v3, vcc
	v_cmp_gt_f32_e32 vcc, s22, v3
	v_mul_f32_e32 v4, 0x4f800000, v3
	s_nop 0
	v_cndmask_b32_e32 v3, v3, v4, vcc
	v_sqrt_f32_e32 v4, v3
	s_nop 0
	v_add_u32_e32 v5, -1, v4
	v_fma_f32 v6, -v5, v4, v3
	v_cmp_ge_f32_e64 s[0:1], 0, v6
	v_add_u32_e32 v6, 1, v4
	s_nop 0
	v_cndmask_b32_e64 v5, v4, v5, s[0:1]
	v_fma_f32 v4, -v6, v4, v3
	v_cmp_lt_f32_e64 s[0:1], 0, v4
	s_nop 1
	v_cndmask_b32_e64 v4, v5, v6, s[0:1]
	v_mul_f32_e32 v5, 0x37800000, v4
	v_cndmask_b32_e32 v4, v4, v5, vcc
	v_cmp_class_f32_e32 vcc, v3, v193
	s_nop 1
	v_cndmask_b32_e32 v3, v4, v3, vcc
	v_cmp_ngt_f32_e32 vcc, s23, v0
	s_nop 1
	v_cndmask_b32_e32 v0, 1.0, v3, vcc
	v_mul_f32_e32 v0, v1, v0
	v_mul_f32_e32 v0, v55, v0
	ds_write_b32 v73, v2 offset:4224
	ds_write_b32 v73, v0 offset:41088
	v_add_f32_e32 v0, v25, v36
	v_mul_f32_e32 v0, 0xbfb8aa3b, v0
	v_exp_f32_e32 v0, v0
	v_add_f32_e32 v1, v9, v38
	v_mul_f32_e32 v1, 0xbfb8aa3b, v1
	v_exp_f32_e32 v1, v1
	v_add_f32_e32 v0, 1.0, v0
	v_rcp_f32_e32 v0, v0
	v_add_f32_e32 v1, 1.0, v1
	v_rcp_f32_e32 v1, v1
	v_mul_f32_e32 v0, v0, v32
	v_mul_f32_e32 v2, 0x3fb8aa3b, v0
	v_add_f32_e32 v0, v0, v0
	v_mul_f32_e32 v3, 0x3fb8aa3b, v0
	v_rndne_f32_e32 v3, v3
	v_fmamk_f32 v4, v3, 0xbf317218, v0
	v_fmac_f32_e32 v4, 0x3102e308, v3
	v_fmamk_f32 v5, v4, 0x395133b1, v192
	v_cmp_eq_f32_e32 vcc, s20, v3
	v_cvt_i32_f32_e32 v3, v3
	v_fmaak_f32 v5, v4, v5, 0x3c0887f9
	v_fmaak_f32 v5, v4, v5, 0x3d2aaa81
	v_fmaak_f32 v5, v4, v5, 0x3e2aaaab
	v_fma_f32 v5, v4, v5, 0.5
	v_ldexp_f32 v3, 1.0, v3
	v_mul_f32_e32 v5, v4, v5
	v_cndmask_b32_e32 v3, v3, v202, vcc
	v_fmac_f32_e32 v4, v4, v5
	v_add_f32_e32 v5, -1.0, v3
	v_fmac_f32_e32 v5, v3, v4
	v_add_f32_e32 v3, v5, v5
	v_cndmask_b32_e32 v3, v5, v3, vcc
	v_cmp_nlt_f32_e32 vcc, s21, v0
	v_exp_f32_e32 v2, v2
	s_nop 0
	v_cndmask_b32_e64 v3, v201, -v3, vcc
	v_cmp_gt_f32_e32 vcc, s22, v3
	v_mul_f32_e32 v4, 0x4f800000, v3
	s_nop 0
	v_cndmask_b32_e32 v3, v3, v4, vcc
	v_sqrt_f32_e32 v4, v3
	s_nop 0
	v_add_u32_e32 v5, -1, v4
	v_fma_f32 v6, -v5, v4, v3
	v_cmp_ge_f32_e64 s[0:1], 0, v6
	v_add_u32_e32 v6, 1, v4
	s_nop 0
	v_cndmask_b32_e64 v5, v4, v5, s[0:1]
	v_fma_f32 v4, -v6, v4, v3
	v_cmp_lt_f32_e64 s[0:1], 0, v4
	s_nop 1
	v_cndmask_b32_e64 v4, v5, v6, s[0:1]
	v_mul_f32_e32 v5, 0x37800000, v4
	v_cndmask_b32_e32 v4, v4, v5, vcc
	v_cmp_class_f32_e32 vcc, v3, v193
	s_nop 1
	v_cndmask_b32_e32 v3, v4, v3, vcc
	v_cmp_ngt_f32_e32 vcc, s23, v0
	s_nop 1
	v_cndmask_b32_e32 v0, 1.0, v3, vcc
	v_mul_f32_e32 v0, v1, v0
	v_mul_f32_e32 v0, v41, v0
	ds_write_b32 v73, v2 offset:4480
	ds_write_b32 v73, v0 offset:41344
	v_add_f32_e32 v0, v26, v36
	v_mul_f32_e32 v0, 0xbfb8aa3b, v0
	v_exp_f32_e32 v0, v0
	v_add_f32_e32 v1, v10, v38
	v_mul_f32_e32 v1, 0xbfb8aa3b, v1
	v_exp_f32_e32 v1, v1
	v_add_f32_e32 v0, 1.0, v0
	v_rcp_f32_e32 v0, v0
	v_add_f32_e32 v1, 1.0, v1
	v_rcp_f32_e32 v1, v1
	v_mul_f32_e32 v0, v0, v32
	v_mul_f32_e32 v2, 0x3fb8aa3b, v0
	v_add_f32_e32 v0, v0, v0
	v_mul_f32_e32 v3, 0x3fb8aa3b, v0
	v_rndne_f32_e32 v3, v3
	v_fmamk_f32 v4, v3, 0xbf317218, v0
	v_fmac_f32_e32 v4, 0x3102e308, v3
	v_fmamk_f32 v5, v4, 0x395133b1, v192
	v_cmp_eq_f32_e32 vcc, s20, v3
	v_cvt_i32_f32_e32 v3, v3
	v_fmaak_f32 v5, v4, v5, 0x3c0887f9
	v_fmaak_f32 v5, v4, v5, 0x3d2aaa81
	v_fmaak_f32 v5, v4, v5, 0x3e2aaaab
	v_fma_f32 v5, v4, v5, 0.5
	v_ldexp_f32 v3, 1.0, v3
	v_mul_f32_e32 v5, v4, v5
	v_cndmask_b32_e32 v3, v3, v202, vcc
	v_fmac_f32_e32 v4, v4, v5
	v_add_f32_e32 v5, -1.0, v3
	v_fmac_f32_e32 v5, v3, v4
	v_add_f32_e32 v3, v5, v5
	v_cndmask_b32_e32 v3, v5, v3, vcc
	v_cmp_nlt_f32_e32 vcc, s21, v0
	v_exp_f32_e32 v2, v2
	s_nop 0
	v_cndmask_b32_e64 v3, v201, -v3, vcc
	v_cmp_gt_f32_e32 vcc, s22, v3
	v_mul_f32_e32 v4, 0x4f800000, v3
	s_nop 0
	v_cndmask_b32_e32 v3, v3, v4, vcc
	v_sqrt_f32_e32 v4, v3
	s_nop 0
	v_add_u32_e32 v5, -1, v4
	v_fma_f32 v6, -v5, v4, v3
	v_cmp_ge_f32_e64 s[0:1], 0, v6
	v_add_u32_e32 v6, 1, v4
	s_nop 0
	v_cndmask_b32_e64 v5, v4, v5, s[0:1]
	v_fma_f32 v4, -v6, v4, v3
	v_cmp_lt_f32_e64 s[0:1], 0, v4
	s_nop 1
	v_cndmask_b32_e64 v4, v5, v6, s[0:1]
	v_mul_f32_e32 v5, 0x37800000, v4
	v_cndmask_b32_e32 v4, v4, v5, vcc
	v_cmp_class_f32_e32 vcc, v3, v193
	s_nop 1
	v_cndmask_b32_e32 v3, v4, v3, vcc
	v_cmp_ngt_f32_e32 vcc, s23, v0
	s_nop 1
	v_cndmask_b32_e32 v0, 1.0, v3, vcc
	v_mul_f32_e32 v0, v1, v0
	v_mul_f32_e32 v0, v57, v0
	ds_write_b32 v73, v2 offset:4736
	ds_write_b32 v73, v0 offset:41600
	v_add_f32_e32 v0, v27, v36
	v_mul_f32_e32 v0, 0xbfb8aa3b, v0
	v_exp_f32_e32 v0, v0
	v_add_f32_e32 v1, v11, v38
	v_mul_f32_e32 v1, 0xbfb8aa3b, v1
	v_exp_f32_e32 v1, v1
	v_add_f32_e32 v0, 1.0, v0
	v_rcp_f32_e32 v0, v0
	v_add_f32_e32 v1, 1.0, v1
	v_rcp_f32_e32 v1, v1
	v_mul_f32_e32 v0, v0, v32
	v_mul_f32_e32 v2, 0x3fb8aa3b, v0
	v_add_f32_e32 v0, v0, v0
	v_mul_f32_e32 v3, 0x3fb8aa3b, v0
	v_rndne_f32_e32 v3, v3
	v_fmamk_f32 v4, v3, 0xbf317218, v0
	v_fmac_f32_e32 v4, 0x3102e308, v3
	v_fmamk_f32 v5, v4, 0x395133b1, v192
	v_cmp_eq_f32_e32 vcc, s20, v3
	v_cvt_i32_f32_e32 v3, v3
	v_fmaak_f32 v5, v4, v5, 0x3c0887f9
	v_fmaak_f32 v5, v4, v5, 0x3d2aaa81
	v_fmaak_f32 v5, v4, v5, 0x3e2aaaab
	v_fma_f32 v5, v4, v5, 0.5
	v_ldexp_f32 v3, 1.0, v3
	v_mul_f32_e32 v5, v4, v5
	v_cndmask_b32_e32 v3, v3, v202, vcc
	v_fmac_f32_e32 v4, v4, v5
	v_add_f32_e32 v5, -1.0, v3
	v_fmac_f32_e32 v5, v3, v4
	v_add_f32_e32 v3, v5, v5
	v_cndmask_b32_e32 v3, v5, v3, vcc
	v_cmp_nlt_f32_e32 vcc, s21, v0
	v_exp_f32_e32 v2, v2
	s_nop 0
	v_cndmask_b32_e64 v3, v201, -v3, vcc
	v_cmp_gt_f32_e32 vcc, s22, v3
	v_mul_f32_e32 v4, 0x4f800000, v3
	s_nop 0
	v_cndmask_b32_e32 v3, v3, v4, vcc
	v_sqrt_f32_e32 v4, v3
	s_nop 0
	v_add_u32_e32 v5, -1, v4
	v_fma_f32 v6, -v5, v4, v3
	v_cmp_ge_f32_e64 s[0:1], 0, v6
	v_add_u32_e32 v6, 1, v4
	s_nop 0
	v_cndmask_b32_e64 v5, v4, v5, s[0:1]
	v_fma_f32 v4, -v6, v4, v3
	v_cmp_lt_f32_e64 s[0:1], 0, v4
	s_nop 1
	v_cndmask_b32_e64 v4, v5, v6, s[0:1]
	v_mul_f32_e32 v5, 0x37800000, v4
	v_cndmask_b32_e32 v4, v4, v5, vcc
	v_cmp_class_f32_e32 vcc, v3, v193
	s_nop 1
	v_cndmask_b32_e32 v3, v4, v3, vcc
	v_cmp_ngt_f32_e32 vcc, s23, v0
	s_nop 1
	v_cndmask_b32_e32 v0, 1.0, v3, vcc
	v_mul_f32_e32 v0, v1, v0
	v_mul_f32_e32 v0, v43, v0
	ds_write_b32 v73, v2 offset:4992
	ds_write_b32 v73, v0 offset:41856
	v_add_f32_e32 v0, v28, v36
	v_mul_f32_e32 v0, 0xbfb8aa3b, v0
	v_exp_f32_e32 v0, v0
	v_add_f32_e32 v1, v12, v38
	v_mul_f32_e32 v1, 0xbfb8aa3b, v1
	v_exp_f32_e32 v1, v1
	v_add_f32_e32 v0, 1.0, v0
	v_rcp_f32_e32 v0, v0
	v_add_f32_e32 v1, 1.0, v1
	v_rcp_f32_e32 v1, v1
	v_mul_f32_e32 v0, v0, v32
	v_mul_f32_e32 v2, 0x3fb8aa3b, v0
	v_add_f32_e32 v0, v0, v0
	v_mul_f32_e32 v3, 0x3fb8aa3b, v0
	v_rndne_f32_e32 v3, v3
	v_fmamk_f32 v4, v3, 0xbf317218, v0
	v_fmac_f32_e32 v4, 0x3102e308, v3
	v_fmamk_f32 v5, v4, 0x395133b1, v192
	v_cmp_eq_f32_e32 vcc, s20, v3
	v_cvt_i32_f32_e32 v3, v3
	v_fmaak_f32 v5, v4, v5, 0x3c0887f9
	v_fmaak_f32 v5, v4, v5, 0x3d2aaa81
	v_fmaak_f32 v5, v4, v5, 0x3e2aaaab
	v_fma_f32 v5, v4, v5, 0.5
	v_ldexp_f32 v3, 1.0, v3
	v_mul_f32_e32 v5, v4, v5
	v_cndmask_b32_e32 v3, v3, v202, vcc
	v_fmac_f32_e32 v4, v4, v5
	v_add_f32_e32 v5, -1.0, v3
	v_fmac_f32_e32 v5, v3, v4
	v_add_f32_e32 v3, v5, v5
	v_cndmask_b32_e32 v3, v5, v3, vcc
	v_cmp_nlt_f32_e32 vcc, s21, v0
	v_exp_f32_e32 v2, v2
	s_nop 0
	v_cndmask_b32_e64 v3, v201, -v3, vcc
	v_cmp_gt_f32_e32 vcc, s22, v3
	v_mul_f32_e32 v4, 0x4f800000, v3
	s_nop 0
	v_cndmask_b32_e32 v3, v3, v4, vcc
	v_sqrt_f32_e32 v4, v3
	s_nop 0
	v_add_u32_e32 v5, -1, v4
	v_fma_f32 v6, -v5, v4, v3
	v_cmp_ge_f32_e64 s[0:1], 0, v6
	v_add_u32_e32 v6, 1, v4
	s_nop 0
	v_cndmask_b32_e64 v5, v4, v5, s[0:1]
	v_fma_f32 v4, -v6, v4, v3
	v_cmp_lt_f32_e64 s[0:1], 0, v4
	s_nop 1
	v_cndmask_b32_e64 v4, v5, v6, s[0:1]
	v_mul_f32_e32 v5, 0x37800000, v4
	v_cndmask_b32_e32 v4, v4, v5, vcc
	v_cmp_class_f32_e32 vcc, v3, v193
	s_nop 1
	v_cndmask_b32_e32 v3, v4, v3, vcc
	v_cmp_ngt_f32_e32 vcc, s23, v0
	s_nop 1
	v_cndmask_b32_e32 v0, 1.0, v3, vcc
	v_mul_f32_e32 v0, v1, v0
	v_mul_f32_e32 v0, v59, v0
	ds_write_b32 v73, v2 offset:6272
	ds_write_b32 v73, v0 offset:43136
	v_add_f32_e32 v0, v29, v36
	v_mul_f32_e32 v0, 0xbfb8aa3b, v0
	v_exp_f32_e32 v0, v0
	v_add_f32_e32 v1, v13, v38
	v_mul_f32_e32 v1, 0xbfb8aa3b, v1
	v_exp_f32_e32 v1, v1
	v_add_f32_e32 v0, 1.0, v0
	v_rcp_f32_e32 v0, v0
	v_add_f32_e32 v1, 1.0, v1
	v_rcp_f32_e32 v1, v1
	v_mul_f32_e32 v0, v0, v32
	v_mul_f32_e32 v2, 0x3fb8aa3b, v0
	v_add_f32_e32 v0, v0, v0
	v_mul_f32_e32 v3, 0x3fb8aa3b, v0
	v_rndne_f32_e32 v3, v3
	v_fmamk_f32 v4, v3, 0xbf317218, v0
	v_fmac_f32_e32 v4, 0x3102e308, v3
	v_fmamk_f32 v5, v4, 0x395133b1, v192
	v_cmp_eq_f32_e32 vcc, s20, v3
	v_cvt_i32_f32_e32 v3, v3
	v_fmaak_f32 v5, v4, v5, 0x3c0887f9
	v_fmaak_f32 v5, v4, v5, 0x3d2aaa81
	v_fmaak_f32 v5, v4, v5, 0x3e2aaaab
	v_fma_f32 v5, v4, v5, 0.5
	v_ldexp_f32 v3, 1.0, v3
	v_mul_f32_e32 v5, v4, v5
	v_cndmask_b32_e32 v3, v3, v202, vcc
	v_fmac_f32_e32 v4, v4, v5
	v_add_f32_e32 v5, -1.0, v3
	v_fmac_f32_e32 v5, v3, v4
	v_add_f32_e32 v3, v5, v5
	v_cndmask_b32_e32 v3, v5, v3, vcc
	v_cmp_nlt_f32_e32 vcc, s21, v0
	v_exp_f32_e32 v2, v2
	s_nop 0
	v_cndmask_b32_e64 v3, v201, -v3, vcc
	v_cmp_gt_f32_e32 vcc, s22, v3
	v_mul_f32_e32 v4, 0x4f800000, v3
	s_nop 0
	v_cndmask_b32_e32 v3, v3, v4, vcc
	v_sqrt_f32_e32 v4, v3
	s_nop 0
	v_add_u32_e32 v5, -1, v4
	v_fma_f32 v6, -v5, v4, v3
	v_cmp_ge_f32_e64 s[0:1], 0, v6
	v_add_u32_e32 v6, 1, v4
	s_nop 0
	v_cndmask_b32_e64 v5, v4, v5, s[0:1]
	v_fma_f32 v4, -v6, v4, v3
	v_cmp_lt_f32_e64 s[0:1], 0, v4
	s_nop 1
	v_cndmask_b32_e64 v4, v5, v6, s[0:1]
	v_mul_f32_e32 v5, 0x37800000, v4
	v_cndmask_b32_e32 v4, v4, v5, vcc
	v_cmp_class_f32_e32 vcc, v3, v193
	s_nop 1
	v_cndmask_b32_e32 v3, v4, v3, vcc
	v_cmp_ngt_f32_e32 vcc, s23, v0
	s_nop 1
	v_cndmask_b32_e32 v0, 1.0, v3, vcc
	v_mul_f32_e32 v0, v1, v0
	v_mul_f32_e32 v0, v45, v0
	ds_write_b32 v73, v2 offset:6528
	ds_write_b32 v73, v0 offset:43392
	v_add_f32_e32 v0, v30, v36
	v_mul_f32_e32 v0, 0xbfb8aa3b, v0
	v_exp_f32_e32 v0, v0
	v_add_f32_e32 v1, v14, v38
	v_mul_f32_e32 v1, 0xbfb8aa3b, v1
	v_exp_f32_e32 v1, v1
	v_add_f32_e32 v0, 1.0, v0
	v_rcp_f32_e32 v0, v0
	v_add_f32_e32 v1, 1.0, v1
	v_rcp_f32_e32 v1, v1
	v_mul_f32_e32 v0, v0, v32
	v_mul_f32_e32 v2, 0x3fb8aa3b, v0
	v_add_f32_e32 v0, v0, v0
	v_mul_f32_e32 v3, 0x3fb8aa3b, v0
	v_rndne_f32_e32 v3, v3
	v_fmamk_f32 v4, v3, 0xbf317218, v0
	v_fmac_f32_e32 v4, 0x3102e308, v3
	v_fmamk_f32 v5, v4, 0x395133b1, v192
	v_cmp_eq_f32_e32 vcc, s20, v3
	v_cvt_i32_f32_e32 v3, v3
	v_fmaak_f32 v5, v4, v5, 0x3c0887f9
	v_fmaak_f32 v5, v4, v5, 0x3d2aaa81
	v_fmaak_f32 v5, v4, v5, 0x3e2aaaab
	v_fma_f32 v5, v4, v5, 0.5
	v_ldexp_f32 v3, 1.0, v3
	v_mul_f32_e32 v5, v4, v5
	v_cndmask_b32_e32 v3, v3, v202, vcc
	v_fmac_f32_e32 v4, v4, v5
	v_add_f32_e32 v5, -1.0, v3
	v_fmac_f32_e32 v5, v3, v4
	v_add_f32_e32 v3, v5, v5
	v_cndmask_b32_e32 v3, v5, v3, vcc
	v_cmp_nlt_f32_e32 vcc, s21, v0
	v_exp_f32_e32 v2, v2
	s_nop 0
	v_cndmask_b32_e64 v3, v201, -v3, vcc
	v_cmp_gt_f32_e32 vcc, s22, v3
	v_mul_f32_e32 v4, 0x4f800000, v3
	s_nop 0
	v_cndmask_b32_e32 v3, v3, v4, vcc
	v_sqrt_f32_e32 v4, v3
	s_nop 0
	v_add_u32_e32 v5, -1, v4
	v_fma_f32 v6, -v5, v4, v3
	v_cmp_ge_f32_e64 s[0:1], 0, v6
	v_add_u32_e32 v6, 1, v4
	s_nop 0
	v_cndmask_b32_e64 v5, v4, v5, s[0:1]
	v_fma_f32 v4, -v6, v4, v3
	v_cmp_lt_f32_e64 s[0:1], 0, v4
	s_nop 1
	v_cndmask_b32_e64 v4, v5, v6, s[0:1]
	v_mul_f32_e32 v5, 0x37800000, v4
	v_cndmask_b32_e32 v4, v4, v5, vcc
	v_cmp_class_f32_e32 vcc, v3, v193
	s_nop 1
	v_cndmask_b32_e32 v3, v4, v3, vcc
	v_cmp_ngt_f32_e32 vcc, s23, v0
	s_nop 1
	v_cndmask_b32_e32 v0, 1.0, v3, vcc
	v_mul_f32_e32 v0, v1, v0
	v_mul_f32_e32 v0, v35, v0
	v_add_u32_e32 v1, 0x1800, v73
	ds_write2_b32 v1, v2, v34 offset0:160 offset1:192
	ds_write_b32 v73, v0 offset:43648
	v_add_f32_e32 v0, v31, v36
	v_mul_f32_e32 v0, 0xbfb8aa3b, v0
	v_exp_f32_e32 v0, v0
	v_add_f32_e32 v1, v15, v38
	v_mul_f32_e32 v1, 0xbfb8aa3b, v1
	v_exp_f32_e32 v1, v1
	v_add_f32_e32 v0, 1.0, v0
	v_rcp_f32_e32 v0, v0
	v_add_f32_e32 v1, 1.0, v1
	v_rcp_f32_e32 v1, v1
	v_mul_f32_e32 v0, v0, v32
	v_mul_f32_e32 v2, 0x3fb8aa3b, v0
	v_add_f32_e32 v0, v0, v0
	v_mul_f32_e32 v3, 0x3fb8aa3b, v0
	v_rndne_f32_e32 v3, v3
	v_fmamk_f32 v4, v3, 0xbf317218, v0
	v_fmac_f32_e32 v4, 0x3102e308, v3
	v_fmamk_f32 v5, v4, 0x395133b1, v192
	v_cmp_eq_f32_e32 vcc, s20, v3
	v_cvt_i32_f32_e32 v3, v3
	v_fmaak_f32 v5, v4, v5, 0x3c0887f9
	v_fmaak_f32 v5, v4, v5, 0x3d2aaa81
	v_fmaak_f32 v5, v4, v5, 0x3e2aaaab
	v_fma_f32 v5, v4, v5, 0.5
	v_ldexp_f32 v3, 1.0, v3
	v_mul_f32_e32 v5, v4, v5
	v_cndmask_b32_e32 v3, v3, v202, vcc
	v_fmac_f32_e32 v4, v4, v5
	v_add_f32_e32 v5, -1.0, v3
	v_fmac_f32_e32 v5, v3, v4
	v_add_f32_e32 v3, v5, v5
	v_cndmask_b32_e32 v3, v5, v3, vcc
	v_cmp_nlt_f32_e32 vcc, s21, v0
	v_exp_f32_e32 v2, v2
	s_nop 0
	v_cndmask_b32_e64 v3, v201, -v3, vcc
	v_cmp_gt_f32_e32 vcc, s22, v3
	v_mul_f32_e32 v4, 0x4f800000, v3
	s_nop 0
	v_cndmask_b32_e32 v3, v3, v4, vcc
	v_sqrt_f32_e32 v4, v3
	s_nop 0
	v_add_u32_e32 v5, -1, v4
	v_fma_f32 v6, -v5, v4, v3
	v_cmp_ge_f32_e64 s[0:1], 0, v6
	v_add_u32_e32 v6, 1, v4
	s_nop 0
	v_cndmask_b32_e64 v5, v4, v5, s[0:1]
	v_fma_f32 v4, -v6, v4, v3
	v_cmp_lt_f32_e64 s[0:1], 0, v4
	s_nop 1
	v_cndmask_b32_e64 v4, v5, v6, s[0:1]
	v_mul_f32_e32 v5, 0x37800000, v4
	v_cndmask_b32_e32 v4, v4, v5, vcc
	v_cmp_class_f32_e32 vcc, v3, v193
	s_nop 1
	v_cndmask_b32_e32 v3, v4, v3, vcc
	v_cmp_ngt_f32_e32 vcc, s23, v0
	s_nop 1
	v_cndmask_b32_e32 v0, 1.0, v3, vcc
	v_mul_f32_e32 v0, v1, v0
	v_mul_f32_e32 v0, v33, v0
	ds_write_b32 v73, v2 offset:7040
	ds_write_b32 v73, v0 offset:43904
	s_waitcnt lgkmcnt(0)
	s_barrier
	s_cbranch_scc1 .LBB0_866
	v_lshl_add_u64 v[0:1], v[64:65], 0, s[4:5]
	global_load_dwordx2 v[98:99], v[0:1], off
	s_cmp_eq_u32 s12, 1
	s_waitcnt vmcnt(0)
	v_fmac_f32_e32 v99, 0, v98
	s_cbranch_scc1 .LBB0_867
	v_add_co_u32_e32 v0, vcc, 0x1000, v0
	s_cmp_eq_u32 s12, 2
	s_nop 0
	v_addc_co_u32_e32 v1, vcc, 0, v1, vcc
	global_load_dwordx2 v[0:1], v[0:1], off
	s_waitcnt vmcnt(0)
	v_fmac_f32_e32 v1, v99, v0
	s_cbranch_scc1 .LBB0_865
	v_readlane_b32 s0, v248, 32
	s_mul_i32 s46, s11, 36
	s_add_i32 s0, s0, s75
	s_mov_b32 s47, s5
	s_sub_i32 s0, s0, s70
	s_lshl_b64 s[44:45], s[46:47], 12
	v_readlane_b32 s1, v249, 45
	s_add_u32 s44, s1, s44
	v_readlane_b32 s1, v249, 46
	v_add_lshl_u32 v96, s13, v141, 3
	s_addc_u32 s45, s1, s45
	v_lshl_add_u64 v[2:3], s[44:45], 0, v[96:97]
	s_mov_b64 s[8:9], 0x1000

.LBB0_908:
	v_add_u32_e32 v137, v135, v134
	ds_read_b128 v[146:149], v135 offset:18432
	ds_read_b128 v[150:153], v137
	s_add_i32 s0, s0, 32
	s_cmp_lt_u32 s0, 48
	s_waitcnt lgkmcnt(0)
	v_mfma_f32_32x32x16_bf16 v[48:63], v[150:153], v[146:149], v[48:63]
	ds_read_b128 v[146:149], v135 offset:23040
	s_waitcnt lgkmcnt(0)
	v_mfma_f32_32x32x16_bf16 v[16:31], v[150:153], v[146:149], v[16:31]
	ds_read_b128 v[146:149], v135 offset:27648
	s_waitcnt lgkmcnt(0)
	v_mfma_f32_32x32x16_bf16 v[32:47], v[150:153], v[146:149], v[32:47]
	ds_read_b128 v[146:149], v135 offset:32256
	ds_read_b128 v[154:157], v135 offset:18464
	s_waitcnt lgkmcnt(1)
	v_mfma_f32_32x32x16_bf16 v[0:15], v[150:153], v[146:149], v[0:15]
	ds_read_b128 v[146:149], v137 offset:32
	ds_read_b128 v[150:153], v135 offset:23072
	s_waitcnt lgkmcnt(0)
	v_mfma_f32_32x32x16_bf16 v[16:31], v[146:149], v[150:153], v[16:31]
	ds_read_b128 v[150:153], v135 offset:27680
	s_waitcnt lgkmcnt(0)
	v_mfma_f32_32x32x16_bf16 v[32:47], v[146:149], v[150:153], v[32:47]
	ds_read_b128 v[150:153], v135 offset:32288
	v_add_u32_e32 v135, 64, v135
	v_mfma_f32_32x32x16_bf16 v[48:63], v[146:149], v[154:157], v[48:63]
	s_waitcnt lgkmcnt(0)
	v_mfma_f32_32x32x16_bf16 v[0:15], v[146:149], v[150:153], v[0:15]
	s_cbranch_scc1 .LBB0_908
	s_cmp_gt_u32 s12, 1
	v_readlane_b32 s0, v248, 27
	s_cselect_b32 s2, 19, 1
	s_or_b32 s3, s13, s0
	v_lshlrev_b32_e32 v137, 11, v96
	v_or_b32_e32 v96, s3, v145
	v_readlane_b32 s16, v251, 20
	v_lshlrev_b64 v[134:135], 2, v[96:97]
	v_readlane_b32 s18, v251, 22
	v_readlane_b32 s19, v251, 23
	s_barrier
	s_nop 0
	v_lshl_add_u64 v[138:139], s[18:19], 0, v[134:135]
	v_readlane_b32 s100, v251, 16
	v_readlane_b32 s101, v251, 17
	s_nop 1
	v_lshl_add_u64 v[220:221], s[100:101], 0, v[134:135]
	v_readlane_b32 s100, v251, 20
	v_readlane_b32 s101, v251, 21
	s_nop 1
	v_lshl_add_u64 v[222:223], s[100:101], 0, v[134:135]
	global_load_dword v224, v[220:221], off
	global_load_dword v225, v[222:223], off
	global_load_dword v226, v[138:139], off offset:128
	global_load_dword v227, v[222:223], off offset:128
	global_load_dword v228, v[220:221], off offset:128
	global_load_dword v96, v[138:139], off
	s_mov_b32 s8, 0x3f2aaaab
	s_mov_b32 s9, 0x3f317218
	s_mov_b32 s10, 0x7f800000
	v_readlane_b32 s20, v251, 24
	s_mov_b32 s20, 0x33800000
	v_readlane_b32 s40, v251, 4
	v_readlane_b32 s52, v251, 16
	v_readlane_b32 s53, v251, 17
	v_readlane_b32 s17, v251, 21
	v_readlane_b32 s21, v251, 25
	s_mov_b32 s21, 0x43000000
	v_readlane_b32 s22, v251, 26
	s_mov_b32 s22, 0x42b17217
	v_readlane_b32 s23, v251, 27
	s_mov_b32 s23, 0xf800000
	v_readlane_b32 s24, v251, 28
	s_mov_b32 s24, 0xc1880000
	v_readlane_b32 s30, v251, 34
	v_readlane_b32 s31, v251, 35
	v_readlane_b32 s25, v251, 29
	v_readlane_b32 s27, v251, 31
	v_readlane_b32 s28, v251, 32
	v_readlane_b32 s29, v251, 33
	v_readlane_b32 s30, v248, 2
	s_cmp_eq_u32 s2, s12
	v_readlane_b32 s31, v248, 3
	s_mov_b32 s28, 0x4800000
	s_movk_i32 s29, 0x47ff
	s_mov_b32 s25, 0x85000
	v_readlane_b32 s27, v248, 10
	v_readlane_b32 s26, v251, 30
	v_readlane_b32 s41, v251, 5
	v_readlane_b32 s42, v251, 6
	v_readlane_b32 s43, v251, 7
	v_readlane_b32 s44, v251, 8
	v_readlane_b32 s45, v251, 9
	v_readlane_b32 s46, v251, 10
	v_readlane_b32 s47, v251, 11
	v_readlane_b32 s48, v251, 12
	v_readlane_b32 s49, v251, 13
	v_readlane_b32 s50, v251, 14
	v_readlane_b32 s51, v251, 15
	v_readlane_b32 s54, v251, 18
	v_readlane_b32 s55, v251, 19
	s_waitcnt vmcnt(0)
	v_mul_f32_e32 v96, 0xbfb8aa3b, v96
	v_exp_f32_e32 v96, v96
	s_nop 0
	v_add_f32_e32 v144, 1.0, v96
	v_add_f32_e32 v138, -1.0, v144
	v_sub_f32_e32 v139, v138, v144
	v_add_f32_e32 v139, 1.0, v139
	v_sub_f32_e32 v138, v96, v138
	v_add_f32_e32 v146, v138, v139
	v_frexp_mant_f32_e32 v138, v144
	v_cmp_gt_f32_e32 vcc, s8, v138
	v_cvt_f64_f32_e32 v[138:139], v144
	v_frexp_exp_i32_f64_e32 v138, v[138:139]
	v_subbrev_co_u32_e32 v152, vcc, 0, v138, vcc
	v_sub_u32_e32 v138, 0, v152
	v_ldexp_f32 v139, v144, v138
	v_add_f32_e32 v144, -1.0, v139
	v_add_f32_e32 v147, 1.0, v139
	v_ldexp_f32 v138, v146, v138
	v_add_f32_e32 v146, 1.0, v144
	v_add_f32_e32 v148, -1.0, v147
	v_sub_f32_e32 v146, v139, v146
	v_sub_f32_e32 v139, v139, v148
	v_add_f32_e32 v146, v138, v146
	v_add_f32_e32 v138, v138, v139
	v_add_f32_e32 v153, v147, v138
	v_rcp_f32_e32 v155, v153
	v_sub_f32_e32 v139, v153, v147
	v_sub_f32_e32 v154, v138, v139
	v_add_f32_e32 v139, v144, v146
	v_sub_f32_e32 v138, v139, v144
	v_mul_f32_e32 v156, v139, v155
	v_sub_f32_e32 v144, v146, v138
	v_mul_f32_e32 v146, v153, v156
	v_fma_f32 v148, v156, v153, -v146
	v_fmac_f32_e32 v148, v156, v154
	v_add_f32_e32 v138, v146, v148
	v_sub_f32_e32 v147, v139, v138
	v_pk_add_f32 v[150:151], v[138:139], v[146:147] neg_lo:[0,1] neg_hi:[0,1]
	v_mov_b32_e32 v149, v138
	v_pk_add_f32 v[138:139], v[150:151], v[148:149] neg_lo:[0,1] neg_hi:[0,1]
	v_cmp_neq_f32_e32 vcc, s10, v96
	v_add_f32_e32 v139, v144, v139
	v_add_f32_e32 v138, v138, v139
	v_add_f32_e32 v139, v147, v138
	v_mul_f32_e32 v144, v155, v139
	v_mul_f32_e32 v146, v153, v144
	v_fma_f32 v148, v144, v153, -v146
	v_fmac_f32_e32 v148, v144, v154
	v_sub_f32_e32 v147, v147, v139
	v_add_f32_e32 v153, v138, v147
	v_add_f32_e32 v138, v146, v148
	v_sub_f32_e32 v147, v139, v138
	v_pk_add_f32 v[150:151], v[138:139], v[146:147] neg_lo:[0,1] neg_hi:[0,1]
	v_mov_b32_e32 v149, v138
	v_pk_add_f32 v[138:139], v[150:151], v[148:149] neg_lo:[0,1] neg_hi:[0,1]
	v_add_f32_e32 v139, v153, v139
	v_add_f32_e32 v138, v138, v139
	v_add_f32_e32 v139, v156, v144
	v_add_f32_e32 v138, v147, v138
	v_sub_f32_e32 v146, v139, v156
	v_mul_f32_e32 v138, v155, v138
	v_sub_f32_e32 v144, v144, v146
	v_add_f32_e32 v144, v144, v138
	v_add_f32_e32 v146, v139, v144
	v_mul_f32_e32 v148, v146, v146
	v_fmamk_f32 v138, v148, 0x3e9b6dac, v191
	v_fmaak_f32 v169, v148, v138, 0x3f2aaada
	v_cvt_f32_i32_e32 v138, v152
	v_sub_f32_e32 v139, v146, v139
	v_sub_f32_e32 v139, v144, v139
	v_ldexp_f32 v144, v139, 1
	v_mul_f32_e32 v139, v146, v148
	v_pk_mul_f32 v[148:149], v[138:139], v[168:169]
	v_ldexp_f32 v147, v146, 1
	v_fma_f32 v146, v138, s9, -v148
	v_fmac_f32_e32 v146, 0xb102e308, v138
	v_pk_add_f32 v[138:139], v[148:149], v[146:147]
	v_mov_b32_e32 v150, v148
	v_sub_f32_e32 v147, v139, v147
	v_sub_f32_e32 v147, v149, v147
	v_add_f32_e32 v151, v144, v147
	v_pk_add_f32 v[148:149], v[138:139], v[148:149] neg_lo:[0,1] neg_hi:[0,1]
	v_pk_add_f32 v[152:153], v[138:139], v[150:151]
	v_mov_b32_e32 v147, v138
	v_mov_b32_e32 v149, v153
	v_pk_add_f32 v[154:155], v[146:147], v[148:149] neg_lo:[0,1] neg_hi:[0,1]
	v_pk_add_f32 v[146:147], v[146:147], v[148:149]
	v_mov_b32_e32 v150, v151
	v_pk_add_f32 v[148:149], v[146:147], v[138:139] op_sel:[1,0] op_sel_hi:[0,1] neg_lo:[0,1] neg_hi:[0,1]
	v_pk_add_f32 v[156:157], v[152:153], v[148:149] op_sel_hi:[1,0] neg_lo:[0,1] neg_hi:[0,1]
	v_mov_b32_e32 v152, v153
	v_mov_b32_e32 v153, v147
	v_pk_mov_b32 v[148:149], v[138:139], v[148:149] op_sel:[1,0]
	v_mov_b32_e32 v151, v138
	v_pk_add_f32 v[148:149], v[152:153], v[148:149] neg_lo:[0,1] neg_hi:[0,1]
	v_mov_b32_e32 v156, v154
	v_pk_add_f32 v[138:139], v[150:151], v[148:149] neg_lo:[0,1] neg_hi:[0,1]
	v_mov_b32_e32 v155, v147
	v_pk_add_f32 v[148:149], v[156:157], v[138:139]
	v_pk_add_f32 v[150:151], v[148:149], v[148:149] op_sel:[0,1] op_sel_hi:[1,0]
	v_pk_add_f32 v[146:147], v[146:147], v[150:151] op_sel:[1,0] op_sel_hi:[0,1]
	v_mov_b32_e32 v149, v146
	v_pk_add_f32 v[152:153], v[148:149], v[154:155] neg_lo:[0,1] neg_hi:[0,1]
	v_mov_b32_e32 v139, v150
	v_sub_f32_e32 v144, v148, v152
	v_pk_add_f32 v[138:139], v[138:139], v[152:153] neg_lo:[0,1] neg_hi:[0,1]
	v_sub_f32_e32 v144, v154, v144
	v_add_f32_e32 v138, v138, v144
	v_add_f32_e32 v138, v138, v139
	v_add_f32_e32 v138, v146, v138
	v_cndmask_b32_e32 v138, v199, v138, vcc
	v_cmp_ngt_f32_e32 vcc, -1.0, v96
	s_nop 1
	v_cndmask_b32_e32 v138, v200, v138, vcc
	v_cmp_neq_f32_e32 vcc, -1.0, v96
	s_nop 1
	v_cndmask_b32_e32 v138, v201, v138, vcc
	v_cmp_lt_f32_e64 vcc, |v96|, s20
	s_nop 1
	v_cndmask_b32_e32 v96, v138, v96, vcc
	v_lshl_add_u64 v[138:139], s[52:53], 0, v[134:135]
	v_mov_b32_e32 v147, v224
	v_lshl_add_u64 v[134:135], s[16:17], 0, v[134:135]
	v_mov_b32_e32 v146, v225
	v_mul_f32_e32 v96, 0xc1000000, v96
	s_waitcnt vmcnt(1)
	v_add_f32_e32 v48, v48, v147
	v_mul_f32_e32 v48, 0xbfb8aa3b, v48
	v_exp_f32_e32 v48, v48
	s_waitcnt vmcnt(0)
	v_add_f32_e32 v32, v32, v146
	v_mul_f32_e32 v32, 0xbfb8aa3b, v32
	v_exp_f32_e32 v32, v32
	v_add_f32_e32 v48, 1.0, v48
	v_rcp_f32_e32 v48, v48
	v_add_f32_e32 v33, v33, v146
	v_add_f32_e32 v32, 1.0, v32
	v_rcp_f32_e32 v32, v32
	v_mul_f32_e32 v48, v48, v96
	v_mul_f32_e32 v134, 0x3fb8aa3b, v48
	v_add_f32_e32 v48, v48, v48
	v_exp_f32_e32 v138, v134
	v_mul_f32_e32 v134, 0x3fb8aa3b, v48
	v_rndne_f32_e32 v134, v134
	v_fmamk_f32 v135, v134, 0xbf317218, v48
	v_fmac_f32_e32 v135, 0x3102e308, v134
	v_fmamk_f32 v139, v135, 0x395133b1, v192
	v_cmp_eq_f32_e32 vcc, s21, v134
	v_cvt_i32_f32_e32 v134, v134
	v_fmaak_f32 v139, v135, v139, 0x3c0887f9
	v_fmaak_f32 v139, v135, v139, 0x3d2aaa81
	v_fmaak_f32 v139, v135, v139, 0x3e2aaaab
	v_fma_f32 v139, v135, v139, 0.5
	v_ldexp_f32 v134, 1.0, v134
	v_mul_f32_e32 v139, v135, v139
	v_cndmask_b32_e32 v134, v134, v202, vcc
	v_fmac_f32_e32 v135, v135, v139
	v_add_f32_e32 v139, -1.0, v134
	v_fmac_f32_e32 v139, v134, v135
	v_add_f32_e32 v134, v139, v139
	v_cndmask_b32_e32 v134, v139, v134, vcc
	v_cmp_nlt_f32_e32 vcc, s22, v48
	v_mul_f32_e32 v33, 0xbfb8aa3b, v33
	v_exp_f32_e32 v33, v33
	v_cndmask_b32_e64 v134, v201, -v134, vcc
	v_cmp_gt_f32_e32 vcc, s23, v134
	v_mul_f32_e32 v135, 0x4f800000, v134
	v_add_f32_e32 v33, 1.0, v33
	v_cndmask_b32_e32 v134, v134, v135, vcc
	v_sqrt_f32_e32 v135, v134
	v_rcp_f32_e32 v33, v33
	v_add_f32_e32 v34, v34, v146
	v_mul_f32_e32 v34, 0xbfb8aa3b, v34
	v_add_u32_e32 v139, -1, v135
	v_fma_f32 v144, -v139, v135, v134
	v_cmp_ge_f32_e64 s[0:1], 0, v144
	v_add_u32_e32 v144, 1, v135
	v_exp_f32_e32 v34, v34
	v_cndmask_b32_e64 v139, v135, v139, s[0:1]
	v_fma_f32 v135, -v144, v135, v134
	v_cmp_lt_f32_e64 s[0:1], 0, v135
	v_add_f32_e32 v34, 1.0, v34
	v_rcp_f32_e32 v34, v34
	v_cndmask_b32_e64 v135, v139, v144, s[0:1]
	v_mul_f32_e32 v139, 0x37800000, v135
	v_cndmask_b32_e32 v135, v135, v139, vcc
	v_cmp_class_f32_e32 vcc, v134, v193
	s_nop 1
	v_cndmask_b32_e32 v134, v135, v134, vcc
	v_cmp_ngt_f32_e32 vcc, s24, v48
	s_nop 1
	v_cndmask_b32_e32 v48, 1.0, v134, vcc
	v_mul_f32_e32 v48, v32, v48
	v_and_b32_e32 v32, 0x100, v136
	v_or3_b32 v32, v137, v145, v32
	v_lshl_add_u32 v144, v32, 2, 0
	v_add_u32_e32 v32, 0x9000, v144
	ds_read2_b32 v[134:135], v32 offset1:32
	s_waitcnt lgkmcnt(0)
	v_mul_f32_e32 v48, v134, v48
	ds_write_b32 v144, v138
	ds_write_b32 v144, v48 offset:36864
	v_add_f32_e32 v48, v49, v147
	v_mul_f32_e32 v48, 0xbfb8aa3b, v48
	v_exp_f32_e32 v48, v48
	s_nop 0
	v_add_f32_e32 v48, 1.0, v48
	v_rcp_f32_e32 v48, v48
	s_nop 0
	v_mul_f32_e32 v48, v48, v96
	v_mul_f32_e32 v49, 0x3fb8aa3b, v48
	v_add_f32_e32 v48, v48, v48
	v_exp_f32_e32 v134, v49
	v_mul_f32_e32 v49, 0x3fb8aa3b, v48
	v_rndne_f32_e32 v49, v49
	v_fmamk_f32 v136, v49, 0xbf317218, v48
	v_fmac_f32_e32 v136, 0x3102e308, v49
	v_fmamk_f32 v137, v136, 0x395133b1, v192
	v_cmp_eq_f32_e32 vcc, s21, v49
	v_cvt_i32_f32_e32 v49, v49
	v_fmaak_f32 v137, v136, v137, 0x3c0887f9
	v_fmaak_f32 v137, v136, v137, 0x3d2aaa81
	v_fmaak_f32 v137, v136, v137, 0x3e2aaaab
	v_fma_f32 v137, v136, v137, 0.5
	v_ldexp_f32 v49, 1.0, v49
	v_mul_f32_e32 v137, v136, v137
	v_cndmask_b32_e32 v49, v49, v202, vcc
	v_fmac_f32_e32 v136, v136, v137
	v_add_f32_e32 v137, -1.0, v49
	v_fmac_f32_e32 v137, v49, v136
	v_add_f32_e32 v49, v137, v137
	v_cndmask_b32_e32 v49, v137, v49, vcc
	v_cmp_nlt_f32_e32 vcc, s22, v48
	s_nop 1
	v_cndmask_b32_e64 v49, v201, -v49, vcc
	v_cmp_gt_f32_e32 vcc, s23, v49
	v_mul_f32_e32 v136, 0x4f800000, v49
	s_nop 0
	v_cndmask_b32_e32 v49, v49, v136, vcc
	v_sqrt_f32_e32 v136, v49
	s_nop 0
	v_add_u32_e32 v137, -1, v136
	v_fma_f32 v138, -v137, v136, v49
	v_cmp_ge_f32_e64 s[0:1], 0, v138
	v_add_u32_e32 v138, 1, v136
	s_nop 0
	v_cndmask_b32_e64 v137, v136, v137, s[0:1]
	v_fma_f32 v136, -v138, v136, v49
	v_cmp_lt_f32_e64 s[0:1], 0, v136
	s_nop 1
	v_cndmask_b32_e64 v136, v137, v138, s[0:1]
	v_mul_f32_e32 v137, 0x37800000, v136
	v_cndmask_b32_e32 v136, v136, v137, vcc
	v_cmp_class_f32_e32 vcc, v49, v193
	s_nop 1
	v_cndmask_b32_e32 v49, v136, v49, vcc
	v_cmp_ngt_f32_e32 vcc, s24, v48
	s_nop 1
	v_cndmask_b32_e32 v48, 1.0, v49, vcc
	v_mul_f32_e32 v33, v33, v48
	ds_read2_b32 v[48:49], v32 offset0:64 offset1:96
	s_waitcnt lgkmcnt(0)
	v_mul_f32_e32 v33, v48, v33
	ds_write_b32 v144, v134 offset:256
	ds_write_b32 v144, v33 offset:37120
	v_add_f32_e32 v33, v50, v147
	v_mul_f32_e32 v33, 0xbfb8aa3b, v33
	v_exp_f32_e32 v33, v33
	s_nop 0
	v_add_f32_e32 v33, 1.0, v33
	v_rcp_f32_e32 v33, v33
	s_nop 0
	v_mul_f32_e32 v33, v33, v96
	v_mul_f32_e32 v48, 0x3fb8aa3b, v33
	v_add_f32_e32 v33, v33, v33
	v_mul_f32_e32 v50, 0x3fb8aa3b, v33
	v_rndne_f32_e32 v50, v50
	v_fmamk_f32 v134, v50, 0xbf317218, v33
	v_fmac_f32_e32 v134, 0x3102e308, v50
	v_fmamk_f32 v136, v134, 0x395133b1, v192
	v_cmp_eq_f32_e32 vcc, s21, v50
	v_cvt_i32_f32_e32 v50, v50
	v_fmaak_f32 v136, v134, v136, 0x3c0887f9
	v_fmaak_f32 v136, v134, v136, 0x3d2aaa81
	v_fmaak_f32 v136, v134, v136, 0x3e2aaaab
	v_fma_f32 v136, v134, v136, 0.5
	v_ldexp_f32 v50, 1.0, v50
	v_mul_f32_e32 v136, v134, v136
	v_cndmask_b32_e32 v50, v50, v202, vcc
	v_fmac_f32_e32 v134, v134, v136
	v_add_f32_e32 v136, -1.0, v50
	v_fmac_f32_e32 v136, v50, v134
	v_add_f32_e32 v50, v136, v136
	v_cndmask_b32_e32 v50, v136, v50, vcc
	v_cmp_nlt_f32_e32 vcc, s22, v33
	v_exp_f32_e32 v48, v48
	s_nop 0
	v_cndmask_b32_e64 v50, v201, -v50, vcc
	v_cmp_gt_f32_e32 vcc, s23, v50
	v_mul_f32_e32 v134, 0x4f800000, v50
	s_nop 0
	v_cndmask_b32_e32 v50, v50, v134, vcc
	v_sqrt_f32_e32 v134, v50
	s_nop 0
	v_add_u32_e32 v136, -1, v134
	v_fma_f32 v137, -v136, v134, v50
	v_cmp_ge_f32_e64 s[0:1], 0, v137
	v_add_u32_e32 v137, 1, v134
	s_nop 0
	v_cndmask_b32_e64 v136, v134, v136, s[0:1]
	v_fma_f32 v134, -v137, v134, v50
	v_cmp_lt_f32_e64 s[0:1], 0, v134
	s_nop 1
	v_cndmask_b32_e64 v134, v136, v137, s[0:1]
	v_mul_f32_e32 v136, 0x37800000, v134
	v_cndmask_b32_e32 v134, v134, v136, vcc
	ds_read2_b32 v[136:137], v32 offset0:128 offset1:160
	v_cmp_class_f32_e32 vcc, v50, v193
	s_nop 1
	v_cndmask_b32_e32 v50, v134, v50, vcc
	v_cmp_ngt_f32_e32 vcc, s24, v33
	s_nop 1
	v_cndmask_b32_e32 v33, 1.0, v50, vcc
	v_mul_f32_e32 v33, v34, v33
	s_waitcnt lgkmcnt(0)
	v_mul_f32_e32 v33, v136, v33
	ds_write_b32 v144, v48 offset:512
	ds_write_b32 v144, v33 offset:37376
	v_add_f32_e32 v33, v51, v147
	v_mul_f32_e32 v33, 0xbfb8aa3b, v33
	v_exp_f32_e32 v33, v33
	v_add_f32_e32 v34, v35, v146
	v_mul_f32_e32 v34, 0xbfb8aa3b, v34
	v_exp_f32_e32 v34, v34
	v_add_f32_e32 v33, 1.0, v33
	v_rcp_f32_e32 v33, v33
	v_add_f32_e32 v34, 1.0, v34
	v_rcp_f32_e32 v34, v34
	v_mul_f32_e32 v33, v33, v96
	v_mul_f32_e32 v35, 0x3fb8aa3b, v33
	v_add_f32_e32 v33, v33, v33
	v_mul_f32_e32 v48, 0x3fb8aa3b, v33
	v_rndne_f32_e32 v48, v48
	v_fmamk_f32 v50, v48, 0xbf317218, v33
	v_fmac_f32_e32 v50, 0x3102e308, v48
	v_fmamk_f32 v51, v50, 0x395133b1, v192
	v_cmp_eq_f32_e32 vcc, s21, v48
	v_cvt_i32_f32_e32 v48, v48
	v_fmaak_f32 v51, v50, v51, 0x3c0887f9
	v_fmaak_f32 v51, v50, v51, 0x3d2aaa81
	v_fmaak_f32 v51, v50, v51, 0x3e2aaaab
	v_fma_f32 v51, v50, v51, 0.5
	v_ldexp_f32 v48, 1.0, v48
	v_mul_f32_e32 v51, v50, v51
	v_cndmask_b32_e32 v48, v48, v202, vcc
	v_fmac_f32_e32 v50, v50, v51
	v_add_f32_e32 v51, -1.0, v48
	v_fmac_f32_e32 v51, v48, v50
	v_add_f32_e32 v48, v51, v51
	v_cndmask_b32_e32 v48, v51, v48, vcc
	v_cmp_nlt_f32_e32 vcc, s22, v33
	v_exp_f32_e32 v35, v35
	s_nop 0
	v_cndmask_b32_e64 v48, v201, -v48, vcc
	v_cmp_gt_f32_e32 vcc, s23, v48
	v_mul_f32_e32 v50, 0x4f800000, v48
	s_nop 0
	v_cndmask_b32_e32 v48, v48, v50, vcc
	v_sqrt_f32_e32 v50, v48
	s_nop 0
	v_add_u32_e32 v51, -1, v50
	v_fma_f32 v134, -v51, v50, v48
	v_cmp_ge_f32_e64 s[0:1], 0, v134
	v_add_u32_e32 v134, 1, v50
	s_nop 0
	v_cndmask_b32_e64 v51, v50, v51, s[0:1]
	v_fma_f32 v50, -v134, v50, v48
	v_cmp_lt_f32_e64 s[0:1], 0, v50
	s_nop 1
	v_cndmask_b32_e64 v50, v51, v134, s[0:1]
	v_mul_f32_e32 v51, 0x37800000, v50
	v_cndmask_b32_e32 v50, v50, v51, vcc
	v_cmp_class_f32_e32 vcc, v48, v193
	s_nop 1
	v_cndmask_b32_e32 v48, v50, v48, vcc
	ds_read2_b32 v[50:51], v32 offset0:192 offset1:224
	v_cmp_ngt_f32_e32 vcc, s24, v33
	s_nop 1
	v_cndmask_b32_e32 v33, 1.0, v48, vcc
	v_mul_f32_e32 v33, v34, v33
	s_waitcnt lgkmcnt(0)
	v_mul_f32_e32 v32, v50, v33
	ds_write_b32 v144, v35 offset:768
	ds_write_b32 v144, v32 offset:37632
	v_add_f32_e32 v32, v52, v147
	v_mul_f32_e32 v32, 0xbfb8aa3b, v32
	v_exp_f32_e32 v32, v32
	v_add_f32_e32 v33, v36, v146
	v_mul_f32_e32 v33, 0xbfb8aa3b, v33
	v_exp_f32_e32 v33, v33
	v_add_f32_e32 v32, 1.0, v32
	v_rcp_f32_e32 v32, v32
	v_add_f32_e32 v33, 1.0, v33
	v_rcp_f32_e32 v33, v33
	v_mul_f32_e32 v32, v32, v96
	v_mul_f32_e32 v34, 0x3fb8aa3b, v32
	v_add_f32_e32 v32, v32, v32
	v_mul_f32_e32 v35, 0x3fb8aa3b, v32
	v_rndne_f32_e32 v35, v35
	v_fmamk_f32 v36, v35, 0xbf317218, v32
	v_fmac_f32_e32 v36, 0x3102e308, v35
	v_fmamk_f32 v48, v36, 0x395133b1, v192
	v_cmp_eq_f32_e32 vcc, s21, v35
	v_cvt_i32_f32_e32 v35, v35
	v_fmaak_f32 v48, v36, v48, 0x3c0887f9
	v_fmaak_f32 v48, v36, v48, 0x3d2aaa81
	v_fmaak_f32 v48, v36, v48, 0x3e2aaaab
	v_fma_f32 v48, v36, v48, 0.5
	v_ldexp_f32 v35, 1.0, v35
	v_mul_f32_e32 v48, v36, v48
	v_cndmask_b32_e32 v35, v35, v202, vcc
	v_fmac_f32_e32 v36, v36, v48
	v_add_f32_e32 v48, -1.0, v35
	v_fmac_f32_e32 v48, v35, v36
	v_add_f32_e32 v35, v48, v48
	v_cndmask_b32_e32 v35, v48, v35, vcc
	v_cmp_nlt_f32_e32 vcc, s22, v32
	v_exp_f32_e32 v34, v34
	s_nop 0
	v_cndmask_b32_e64 v35, v201, -v35, vcc
	v_cmp_gt_f32_e32 vcc, s23, v35
	v_mul_f32_e32 v36, 0x4f800000, v35
	s_nop 0
	v_cndmask_b32_e32 v35, v35, v36, vcc
	v_sqrt_f32_e32 v36, v35
	s_nop 0
	v_add_u32_e32 v48, -1, v36
	v_fma_f32 v50, -v48, v36, v35
	v_cmp_ge_f32_e64 s[0:1], 0, v50
	v_add_u32_e32 v50, 1, v36
	s_nop 0
	v_cndmask_b32_e64 v48, v36, v48, s[0:1]
	v_fma_f32 v36, -v50, v36, v35
	v_cmp_lt_f32_e64 s[0:1], 0, v36
	s_nop 1
	v_cndmask_b32_e64 v36, v48, v50, s[0:1]
	v_mul_f32_e32 v48, 0x37800000, v36
	v_cndmask_b32_e32 v36, v36, v48, vcc
	v_cmp_class_f32_e32 vcc, v35, v193
	s_nop 1
	v_cndmask_b32_e32 v35, v36, v35, vcc
	v_cmp_ngt_f32_e32 vcc, s24, v32
	s_nop 1
	v_cndmask_b32_e32 v32, 1.0, v35, vcc
	v_mul_f32_e32 v33, v33, v32
	v_add_u32_e32 v32, 0x9800, v144
	ds_read2_b32 v[138:139], v32 offset1:32
	s_waitcnt lgkmcnt(0)
	v_mul_f32_e32 v33, v138, v33
	ds_write_b32 v144, v34 offset:2048
	ds_write_b32 v144, v33 offset:38912
	v_add_f32_e32 v33, v53, v147
	v_mul_f32_e32 v33, 0xbfb8aa3b, v33
	v_exp_f32_e32 v33, v33
	v_add_f32_e32 v34, v37, v146
	v_mul_f32_e32 v34, 0xbfb8aa3b, v34
	v_exp_f32_e32 v34, v34
	v_add_f32_e32 v33, 1.0, v33
	v_rcp_f32_e32 v33, v33
	v_add_f32_e32 v34, 1.0, v34
	v_rcp_f32_e32 v34, v34
	v_mul_f32_e32 v33, v33, v96
	v_mul_f32_e32 v35, 0x3fb8aa3b, v33
	v_add_f32_e32 v33, v33, v33
	v_mul_f32_e32 v36, 0x3fb8aa3b, v33
	v_rndne_f32_e32 v36, v36
	v_fmamk_f32 v37, v36, 0xbf317218, v33
	v_fmac_f32_e32 v37, 0x3102e308, v36
	v_fmamk_f32 v48, v37, 0x395133b1, v192
	v_cmp_eq_f32_e32 vcc, s21, v36
	v_cvt_i32_f32_e32 v36, v36
	v_fmaak_f32 v48, v37, v48, 0x3c0887f9
	v_fmaak_f32 v48, v37, v48, 0x3d2aaa81
	v_fmaak_f32 v48, v37, v48, 0x3e2aaaab
	v_fma_f32 v48, v37, v48, 0.5
	v_ldexp_f32 v36, 1.0, v36
	v_mul_f32_e32 v48, v37, v48
	v_cndmask_b32_e32 v36, v36, v202, vcc
	v_fmac_f32_e32 v37, v37, v48
	v_add_f32_e32 v48, -1.0, v36
	v_fmac_f32_e32 v48, v36, v37
	v_add_f32_e32 v36, v48, v48
	v_cndmask_b32_e32 v36, v48, v36, vcc
	v_cmp_nlt_f32_e32 vcc, s22, v33
	v_exp_f32_e32 v35, v35
	s_nop 0
	v_cndmask_b32_e64 v36, v201, -v36, vcc
	v_cmp_gt_f32_e32 vcc, s23, v36
	v_mul_f32_e32 v37, 0x4f800000, v36
	s_nop 0
	v_cndmask_b32_e32 v36, v36, v37, vcc
	v_sqrt_f32_e32 v37, v36
	s_nop 0
	v_add_u32_e32 v48, -1, v37
	v_fma_f32 v50, -v48, v37, v36
	v_cmp_ge_f32_e64 s[0:1], 0, v50
	v_add_u32_e32 v50, 1, v37
	s_nop 0
	v_cndmask_b32_e64 v48, v37, v48, s[0:1]
	v_fma_f32 v37, -v50, v37, v36
	v_cmp_lt_f32_e64 s[0:1], 0, v37
	s_nop 1
	v_cndmask_b32_e64 v37, v48, v50, s[0:1]
	v_mul_f32_e32 v48, 0x37800000, v37
	v_cndmask_b32_e32 v37, v37, v48, vcc
	v_cmp_class_f32_e32 vcc, v36, v193
	s_nop 1
	v_cndmask_b32_e32 v36, v37, v36, vcc
	v_cmp_ngt_f32_e32 vcc, s24, v33
	s_nop 1
	v_cndmask_b32_e32 v33, 1.0, v36, vcc
	ds_read2_b32 v[36:37], v32 offset0:64 offset1:96
	v_mul_f32_e32 v33, v34, v33
	v_add_f32_e32 v34, v38, v146
	v_mul_f32_e32 v34, 0xbfb8aa3b, v34
	v_exp_f32_e32 v34, v34
	s_waitcnt lgkmcnt(0)
	v_mul_f32_e32 v33, v36, v33
	ds_write_b32 v144, v35 offset:2304
	ds_write_b32 v144, v33 offset:39168
	v_add_f32_e32 v33, v54, v147
	v_mul_f32_e32 v33, 0xbfb8aa3b, v33
	v_exp_f32_e32 v33, v33
	v_add_f32_e32 v34, 1.0, v34
	v_rcp_f32_e32 v34, v34
	ds_read2_b32 v[52:53], v32 offset0:128 offset1:160
	v_add_f32_e32 v33, 1.0, v33
	v_rcp_f32_e32 v33, v33
	s_nop 0
	v_mul_f32_e32 v33, v33, v96
	v_mul_f32_e32 v35, 0x3fb8aa3b, v33
	v_add_f32_e32 v33, v33, v33
	v_mul_f32_e32 v36, 0x3fb8aa3b, v33
	v_rndne_f32_e32 v36, v36
	v_fmamk_f32 v38, v36, 0xbf317218, v33
	v_fmac_f32_e32 v38, 0x3102e308, v36
	v_fmamk_f32 v48, v38, 0x395133b1, v192
	v_cmp_eq_f32_e32 vcc, s21, v36
	v_cvt_i32_f32_e32 v36, v36
	v_fmaak_f32 v48, v38, v48, 0x3c0887f9
	v_fmaak_f32 v48, v38, v48, 0x3d2aaa81
	v_fmaak_f32 v48, v38, v48, 0x3e2aaaab
	v_fma_f32 v48, v38, v48, 0.5
	v_ldexp_f32 v36, 1.0, v36
	v_mul_f32_e32 v48, v38, v48
	v_cndmask_b32_e32 v36, v36, v202, vcc
	v_fmac_f32_e32 v38, v38, v48
	v_add_f32_e32 v48, -1.0, v36
	v_fmac_f32_e32 v48, v36, v38
	v_add_f32_e32 v36, v48, v48
	v_cndmask_b32_e32 v36, v48, v36, vcc
	v_cmp_nlt_f32_e32 vcc, s22, v33
	v_exp_f32_e32 v35, v35
	s_nop 0
	v_cndmask_b32_e64 v36, v201, -v36, vcc
	v_cmp_gt_f32_e32 vcc, s23, v36
	v_mul_f32_e32 v38, 0x4f800000, v36
	s_nop 0
	v_cndmask_b32_e32 v36, v36, v38, vcc
	v_sqrt_f32_e32 v38, v36
	s_nop 0
	v_add_u32_e32 v48, -1, v38
	v_fma_f32 v50, -v48, v38, v36
	v_cmp_ge_f32_e64 s[0:1], 0, v50
	v_add_u32_e32 v50, 1, v38
	s_nop 0
	v_cndmask_b32_e64 v48, v38, v48, s[0:1]
	v_fma_f32 v38, -v50, v38, v36
	v_cmp_lt_f32_e64 s[0:1], 0, v38
	s_nop 1
	v_cndmask_b32_e64 v38, v48, v50, s[0:1]
	v_mul_f32_e32 v48, 0x37800000, v38
	v_cndmask_b32_e32 v38, v38, v48, vcc
	v_cmp_class_f32_e32 vcc, v36, v193
	s_nop 1
	v_cndmask_b32_e32 v36, v38, v36, vcc
	v_cmp_ngt_f32_e32 vcc, s24, v33
	s_nop 1
	v_cndmask_b32_e32 v33, 1.0, v36, vcc
	v_mul_f32_e32 v33, v34, v33
	s_waitcnt lgkmcnt(0)
	v_mul_f32_e32 v33, v52, v33
	ds_write_b32 v144, v35 offset:2560
	ds_write_b32 v144, v33 offset:39424
	v_add_f32_e32 v33, v55, v147
	v_mul_f32_e32 v33, 0xbfb8aa3b, v33
	v_exp_f32_e32 v33, v33
	v_add_f32_e32 v34, v39, v146
	v_mul_f32_e32 v34, 0xbfb8aa3b, v34
	v_exp_f32_e32 v34, v34
	v_add_f32_e32 v33, 1.0, v33
	v_rcp_f32_e32 v33, v33
	v_add_f32_e32 v34, 1.0, v34
	v_rcp_f32_e32 v34, v34
	v_mul_f32_e32 v33, v33, v96
	v_mul_f32_e32 v35, 0x3fb8aa3b, v33
	v_add_f32_e32 v33, v33, v33
	v_mul_f32_e32 v36, 0x3fb8aa3b, v33
	v_rndne_f32_e32 v36, v36
	v_fmamk_f32 v38, v36, 0xbf317218, v33
	v_fmac_f32_e32 v38, 0x3102e308, v36
	v_fmamk_f32 v39, v38, 0x395133b1, v192
	v_cmp_eq_f32_e32 vcc, s21, v36
	v_cvt_i32_f32_e32 v36, v36
	v_fmaak_f32 v39, v38, v39, 0x3c0887f9
	v_fmaak_f32 v39, v38, v39, 0x3d2aaa81
	v_fmaak_f32 v39, v38, v39, 0x3e2aaaab
	v_fma_f32 v39, v38, v39, 0.5
	v_ldexp_f32 v36, 1.0, v36
	v_mul_f32_e32 v39, v38, v39
	v_cndmask_b32_e32 v36, v36, v202, vcc
	v_fmac_f32_e32 v38, v38, v39
	v_add_f32_e32 v39, -1.0, v36
	v_fmac_f32_e32 v39, v36, v38
	v_add_f32_e32 v36, v39, v39
	v_cndmask_b32_e32 v36, v39, v36, vcc
	v_cmp_nlt_f32_e32 vcc, s22, v33
	v_exp_f32_e32 v35, v35
	s_nop 0
	v_cndmask_b32_e64 v36, v201, -v36, vcc
	v_cmp_gt_f32_e32 vcc, s23, v36
	v_mul_f32_e32 v38, 0x4f800000, v36
	s_nop 0
	v_cndmask_b32_e32 v36, v36, v38, vcc
	v_sqrt_f32_e32 v38, v36
	s_nop 0
	v_add_u32_e32 v39, -1, v38
	v_fma_f32 v48, -v39, v38, v36
	v_cmp_ge_f32_e64 s[0:1], 0, v48
	v_add_u32_e32 v48, 1, v38
	s_nop 0
	v_cndmask_b32_e64 v39, v38, v39, s[0:1]
	v_fma_f32 v38, -v48, v38, v36
	v_cmp_lt_f32_e64 s[0:1], 0, v38
	s_nop 1
	v_cndmask_b32_e64 v38, v39, v48, s[0:1]
	v_mul_f32_e32 v39, 0x37800000, v38
	v_cndmask_b32_e32 v38, v38, v39, vcc
	v_cmp_class_f32_e32 vcc, v36, v193
	s_nop 1
	v_cndmask_b32_e32 v36, v38, v36, vcc
	ds_read2_b32 v[38:39], v32 offset0:192 offset1:224
	v_cmp_ngt_f32_e32 vcc, s24, v33
	s_nop 1
	v_cndmask_b32_e32 v33, 1.0, v36, vcc
	v_mul_f32_e32 v33, v34, v33
	s_waitcnt lgkmcnt(0)
	v_mul_f32_e32 v32, v38, v33
	ds_write_b32 v144, v35 offset:2816
	ds_write_b32 v144, v32 offset:39680
	v_add_f32_e32 v32, v56, v147
	v_mul_f32_e32 v32, 0xbfb8aa3b, v32
	v_exp_f32_e32 v32, v32
	v_add_f32_e32 v33, v40, v146
	v_mul_f32_e32 v33, 0xbfb8aa3b, v33
	v_exp_f32_e32 v33, v33
	v_add_f32_e32 v32, 1.0, v32
	v_rcp_f32_e32 v32, v32
	v_add_f32_e32 v33, 1.0, v33
	v_rcp_f32_e32 v33, v33
	v_mul_f32_e32 v32, v32, v96
	v_mul_f32_e32 v34, 0x3fb8aa3b, v32
	v_add_f32_e32 v32, v32, v32
	v_mul_f32_e32 v35, 0x3fb8aa3b, v32
	v_rndne_f32_e32 v35, v35
	v_fmamk_f32 v36, v35, 0xbf317218, v32
	v_fmac_f32_e32 v36, 0x3102e308, v35
	v_fmamk_f32 v38, v36, 0x395133b1, v192
	v_cmp_eq_f32_e32 vcc, s21, v35
	v_cvt_i32_f32_e32 v35, v35
	v_fmaak_f32 v38, v36, v38, 0x3c0887f9
	v_fmaak_f32 v38, v36, v38, 0x3d2aaa81
	v_fmaak_f32 v38, v36, v38, 0x3e2aaaab
	v_fma_f32 v38, v36, v38, 0.5
	v_ldexp_f32 v35, 1.0, v35
	v_mul_f32_e32 v38, v36, v38
	v_cndmask_b32_e32 v35, v35, v202, vcc
	v_fmac_f32_e32 v36, v36, v38
	v_add_f32_e32 v38, -1.0, v35
	v_fmac_f32_e32 v38, v35, v36
	v_add_f32_e32 v35, v38, v38
	v_cndmask_b32_e32 v35, v38, v35, vcc
	v_cmp_nlt_f32_e32 vcc, s22, v32
	v_exp_f32_e32 v34, v34
	s_nop 0
	v_cndmask_b32_e64 v35, v201, -v35, vcc
	v_cmp_gt_f32_e32 vcc, s23, v35
	v_mul_f32_e32 v36, 0x4f800000, v35
	s_nop 0
	v_cndmask_b32_e32 v35, v35, v36, vcc
	v_sqrt_f32_e32 v36, v35
	s_nop 0
	v_add_u32_e32 v38, -1, v36
	v_fma_f32 v40, -v38, v36, v35
	v_cmp_ge_f32_e64 s[0:1], 0, v40
	v_add_u32_e32 v40, 1, v36
	s_nop 0
	v_cndmask_b32_e64 v38, v36, v38, s[0:1]
	v_fma_f32 v36, -v40, v36, v35
	v_cmp_lt_f32_e64 s[0:1], 0, v36
	s_nop 1
	v_cndmask_b32_e64 v36, v38, v40, s[0:1]
	v_mul_f32_e32 v38, 0x37800000, v36
	v_cndmask_b32_e32 v36, v36, v38, vcc
	v_cmp_class_f32_e32 vcc, v35, v193
	s_nop 1
	v_cndmask_b32_e32 v35, v36, v35, vcc
	v_cmp_ngt_f32_e32 vcc, s24, v32
	s_nop 1
	v_cndmask_b32_e32 v32, 1.0, v35, vcc
	v_mul_f32_e32 v33, v33, v32
	v_add_u32_e32 v32, 0xa000, v144
	ds_read2_b32 v[54:55], v32 offset1:32
	s_waitcnt lgkmcnt(0)
	v_mul_f32_e32 v33, v54, v33
	ds_write_b32 v144, v34 offset:4096
	ds_write_b32 v144, v33 offset:40960
	v_add_f32_e32 v33, v57, v147
	v_mul_f32_e32 v33, 0xbfb8aa3b, v33
	v_exp_f32_e32 v33, v33
	v_add_f32_e32 v34, v41, v146
	v_mul_f32_e32 v34, 0xbfb8aa3b, v34
	v_exp_f32_e32 v34, v34
	v_add_f32_e32 v33, 1.0, v33
	v_rcp_f32_e32 v33, v33
	v_add_f32_e32 v34, 1.0, v34
	v_rcp_f32_e32 v34, v34
	v_mul_f32_e32 v33, v33, v96
	v_mul_f32_e32 v35, 0x3fb8aa3b, v33
	v_add_f32_e32 v33, v33, v33
	v_mul_f32_e32 v36, 0x3fb8aa3b, v33
	v_rndne_f32_e32 v36, v36
	v_fmamk_f32 v38, v36, 0xbf317218, v33
	v_fmac_f32_e32 v38, 0x3102e308, v36
	v_fmamk_f32 v40, v38, 0x395133b1, v192
	v_cmp_eq_f32_e32 vcc, s21, v36
	v_cvt_i32_f32_e32 v36, v36
	v_fmaak_f32 v40, v38, v40, 0x3c0887f9
	v_fmaak_f32 v40, v38, v40, 0x3d2aaa81
	v_fmaak_f32 v40, v38, v40, 0x3e2aaaab
	v_fma_f32 v40, v38, v40, 0.5
	v_ldexp_f32 v36, 1.0, v36
	v_mul_f32_e32 v40, v38, v40
	v_cndmask_b32_e32 v36, v36, v202, vcc
	v_fmac_f32_e32 v38, v38, v40
	v_add_f32_e32 v40, -1.0, v36
	v_fmac_f32_e32 v40, v36, v38
	v_add_f32_e32 v36, v40, v40
	v_cndmask_b32_e32 v36, v40, v36, vcc
	v_cmp_nlt_f32_e32 vcc, s22, v33
	v_exp_f32_e32 v35, v35
	s_nop 0
	v_cndmask_b32_e64 v36, v201, -v36, vcc
	v_cmp_gt_f32_e32 vcc, s23, v36
	v_mul_f32_e32 v38, 0x4f800000, v36
	s_nop 0
	v_cndmask_b32_e32 v36, v36, v38, vcc
	v_sqrt_f32_e32 v38, v36
	s_nop 0
	v_add_u32_e32 v40, -1, v38
	v_fma_f32 v41, -v40, v38, v36
	v_cmp_ge_f32_e64 s[0:1], 0, v41
	v_add_u32_e32 v41, 1, v38
	s_nop 0
	v_cndmask_b32_e64 v40, v38, v40, s[0:1]
	v_fma_f32 v38, -v41, v38, v36
	v_cmp_lt_f32_e64 s[0:1], 0, v38
	s_nop 1
	v_cndmask_b32_e64 v38, v40, v41, s[0:1]
	v_mul_f32_e32 v40, 0x37800000, v38
	v_cndmask_b32_e32 v38, v38, v40, vcc
	ds_read2_b32 v[40:41], v32 offset0:64 offset1:96
	v_cmp_class_f32_e32 vcc, v36, v193
	s_nop 1
	v_cndmask_b32_e32 v36, v38, v36, vcc
	v_cmp_ngt_f32_e32 vcc, s24, v33
	s_nop 1
	v_cndmask_b32_e32 v33, 1.0, v36, vcc
	v_mul_f32_e32 v33, v34, v33
	s_waitcnt lgkmcnt(0)
	v_mul_f32_e32 v33, v40, v33
	ds_write_b32 v144, v35 offset:4352
	ds_write_b32 v144, v33 offset:41216
	v_add_f32_e32 v33, v58, v147
	v_mul_f32_e32 v33, 0xbfb8aa3b, v33
	v_exp_f32_e32 v33, v33
	v_add_f32_e32 v34, v42, v146
	v_mul_f32_e32 v34, 0xbfb8aa3b, v34
	v_exp_f32_e32 v34, v34
	v_add_f32_e32 v33, 1.0, v33
	v_rcp_f32_e32 v33, v33
	ds_read2_b32 v[56:57], v32 offset0:128 offset1:160
	v_add_f32_e32 v34, 1.0, v34
	v_rcp_f32_e32 v34, v34
	v_mul_f32_e32 v33, v33, v96
	v_mul_f32_e32 v35, 0x3fb8aa3b, v33
	v_add_f32_e32 v33, v33, v33
	v_mul_f32_e32 v36, 0x3fb8aa3b, v33
	v_rndne_f32_e32 v36, v36
	v_fmamk_f32 v38, v36, 0xbf317218, v33
	v_fmac_f32_e32 v38, 0x3102e308, v36
	v_fmamk_f32 v40, v38, 0x395133b1, v192
	v_cmp_eq_f32_e32 vcc, s21, v36
	v_cvt_i32_f32_e32 v36, v36
	v_fmaak_f32 v40, v38, v40, 0x3c0887f9
	v_fmaak_f32 v40, v38, v40, 0x3d2aaa81
	v_fmaak_f32 v40, v38, v40, 0x3e2aaaab
	v_fma_f32 v40, v38, v40, 0.5
	v_ldexp_f32 v36, 1.0, v36
	v_mul_f32_e32 v40, v38, v40
	v_cndmask_b32_e32 v36, v36, v202, vcc
	v_fmac_f32_e32 v38, v38, v40
	v_add_f32_e32 v40, -1.0, v36
	v_fmac_f32_e32 v40, v36, v38
	v_add_f32_e32 v36, v40, v40
	v_cndmask_b32_e32 v36, v40, v36, vcc
	v_cmp_nlt_f32_e32 vcc, s22, v33
	v_exp_f32_e32 v35, v35
	s_nop 0
	v_cndmask_b32_e64 v36, v201, -v36, vcc
	v_cmp_gt_f32_e32 vcc, s23, v36
	v_mul_f32_e32 v38, 0x4f800000, v36
	s_nop 0
	v_cndmask_b32_e32 v36, v36, v38, vcc
	v_sqrt_f32_e32 v38, v36
	s_nop 0
	v_add_u32_e32 v40, -1, v38
	v_fma_f32 v42, -v40, v38, v36
	v_cmp_ge_f32_e64 s[0:1], 0, v42
	v_add_u32_e32 v42, 1, v38
	s_nop 0
	v_cndmask_b32_e64 v40, v38, v40, s[0:1]
	v_fma_f32 v38, -v42, v38, v36
	v_cmp_lt_f32_e64 s[0:1], 0, v38
	s_nop 1
	v_cndmask_b32_e64 v38, v40, v42, s[0:1]
	v_mul_f32_e32 v40, 0x37800000, v38
	v_cndmask_b32_e32 v38, v38, v40, vcc
	v_cmp_class_f32_e32 vcc, v36, v193
	s_nop 1
	v_cndmask_b32_e32 v36, v38, v36, vcc
	v_cmp_ngt_f32_e32 vcc, s24, v33
	s_nop 1
	v_cndmask_b32_e32 v33, 1.0, v36, vcc
	v_mul_f32_e32 v33, v34, v33
	s_waitcnt lgkmcnt(0)
	v_mul_f32_e32 v33, v56, v33
	ds_write_b32 v144, v35 offset:4608
	ds_write_b32 v144, v33 offset:41472
	v_add_f32_e32 v33, v59, v147
	v_mul_f32_e32 v33, 0xbfb8aa3b, v33
	v_exp_f32_e32 v33, v33
	v_add_f32_e32 v34, v43, v146
	v_mul_f32_e32 v34, 0xbfb8aa3b, v34
	v_exp_f32_e32 v34, v34
	v_add_f32_e32 v33, 1.0, v33
	v_rcp_f32_e32 v33, v33
	v_add_f32_e32 v34, 1.0, v34
	v_rcp_f32_e32 v34, v34
	v_mul_f32_e32 v33, v33, v96
	v_mul_f32_e32 v35, 0x3fb8aa3b, v33
	v_add_f32_e32 v33, v33, v33
	v_mul_f32_e32 v36, 0x3fb8aa3b, v33
	v_rndne_f32_e32 v36, v36
	v_fmamk_f32 v38, v36, 0xbf317218, v33
	v_fmac_f32_e32 v38, 0x3102e308, v36
	v_fmamk_f32 v40, v38, 0x395133b1, v192
	v_cmp_eq_f32_e32 vcc, s21, v36
	v_cvt_i32_f32_e32 v36, v36
	v_fmaak_f32 v40, v38, v40, 0x3c0887f9
	v_fmaak_f32 v40, v38, v40, 0x3d2aaa81
	v_fmaak_f32 v40, v38, v40, 0x3e2aaaab
	v_fma_f32 v40, v38, v40, 0.5
	v_ldexp_f32 v36, 1.0, v36
	v_mul_f32_e32 v40, v38, v40
	v_cndmask_b32_e32 v36, v36, v202, vcc
	v_fmac_f32_e32 v38, v38, v40
	v_add_f32_e32 v40, -1.0, v36
	v_fmac_f32_e32 v40, v36, v38
	v_add_f32_e32 v36, v40, v40
	v_cndmask_b32_e32 v36, v40, v36, vcc
	v_cmp_nlt_f32_e32 vcc, s22, v33
	v_exp_f32_e32 v35, v35
	s_nop 0
	v_cndmask_b32_e64 v36, v201, -v36, vcc
	v_cmp_gt_f32_e32 vcc, s23, v36
	v_mul_f32_e32 v38, 0x4f800000, v36
	s_nop 0
	v_cndmask_b32_e32 v36, v36, v38, vcc
	v_sqrt_f32_e32 v38, v36
	s_nop 0
	v_add_u32_e32 v40, -1, v38
	v_fma_f32 v42, -v40, v38, v36
	v_cmp_ge_f32_e64 s[0:1], 0, v42
	v_add_u32_e32 v42, 1, v38
	s_nop 0
	v_cndmask_b32_e64 v40, v38, v40, s[0:1]
	v_fma_f32 v38, -v42, v38, v36
	v_cmp_lt_f32_e64 s[0:1], 0, v38
	s_nop 1
	v_cndmask_b32_e64 v38, v40, v42, s[0:1]
	v_mul_f32_e32 v40, 0x37800000, v38
	ds_read2_b32 v[42:43], v32 offset0:192 offset1:224
	v_cndmask_b32_e32 v38, v38, v40, vcc
	v_cmp_class_f32_e32 vcc, v36, v193
	s_nop 1
	v_cndmask_b32_e32 v36, v38, v36, vcc
	v_cmp_ngt_f32_e32 vcc, s24, v33
	s_nop 1
	v_cndmask_b32_e32 v33, 1.0, v36, vcc
	v_mul_f32_e32 v33, v34, v33
	s_waitcnt lgkmcnt(0)
	v_mul_f32_e32 v32, v42, v33
	ds_write_b32 v144, v35 offset:4864
	ds_write_b32 v144, v32 offset:41728
	v_add_f32_e32 v32, v60, v147
	v_mul_f32_e32 v32, 0xbfb8aa3b, v32
	v_exp_f32_e32 v32, v32
	v_add_f32_e32 v33, v44, v146
	v_mul_f32_e32 v33, 0xbfb8aa3b, v33
	v_exp_f32_e32 v33, v33
	v_add_f32_e32 v32, 1.0, v32
	v_rcp_f32_e32 v32, v32
	v_add_f32_e32 v33, 1.0, v33
	v_rcp_f32_e32 v33, v33
	v_mul_f32_e32 v32, v32, v96
	v_mul_f32_e32 v34, 0x3fb8aa3b, v32
	v_add_f32_e32 v32, v32, v32
	v_mul_f32_e32 v35, 0x3fb8aa3b, v32
	v_rndne_f32_e32 v35, v35
	v_fmamk_f32 v36, v35, 0xbf317218, v32
	v_fmac_f32_e32 v36, 0x3102e308, v35
	v_fmamk_f32 v38, v36, 0x395133b1, v192
	v_cmp_eq_f32_e32 vcc, s21, v35
	v_cvt_i32_f32_e32 v35, v35
	v_fmaak_f32 v38, v36, v38, 0x3c0887f9
	v_fmaak_f32 v38, v36, v38, 0x3d2aaa81
	v_fmaak_f32 v38, v36, v38, 0x3e2aaaab
	v_fma_f32 v38, v36, v38, 0.5
	v_ldexp_f32 v35, 1.0, v35
	v_mul_f32_e32 v38, v36, v38
	v_cndmask_b32_e32 v35, v35, v202, vcc
	v_fmac_f32_e32 v36, v36, v38
	v_add_f32_e32 v38, -1.0, v35
	v_fmac_f32_e32 v38, v35, v36
	v_add_f32_e32 v35, v38, v38
	v_cndmask_b32_e32 v35, v38, v35, vcc
	v_cmp_nlt_f32_e32 vcc, s22, v32
	v_exp_f32_e32 v34, v34
	s_nop 0
	v_cndmask_b32_e64 v35, v201, -v35, vcc
	v_cmp_gt_f32_e32 vcc, s23, v35
	v_mul_f32_e32 v36, 0x4f800000, v35
	s_nop 0
	v_cndmask_b32_e32 v35, v35, v36, vcc
	v_sqrt_f32_e32 v36, v35
	s_nop 0
	v_add_u32_e32 v38, -1, v36
	v_fma_f32 v40, -v38, v36, v35
	v_cmp_ge_f32_e64 s[0:1], 0, v40
	v_add_u32_e32 v40, 1, v36
	s_nop 0
	v_cndmask_b32_e64 v38, v36, v38, s[0:1]
	v_fma_f32 v36, -v40, v36, v35
	v_cmp_lt_f32_e64 s[0:1], 0, v36
	s_nop 1
	v_cndmask_b32_e64 v36, v38, v40, s[0:1]
	v_mul_f32_e32 v38, 0x37800000, v36
	v_cndmask_b32_e32 v36, v36, v38, vcc
	v_cmp_class_f32_e32 vcc, v35, v193
	s_nop 1
	v_cndmask_b32_e32 v35, v36, v35, vcc
	v_cmp_ngt_f32_e32 vcc, s24, v32
	s_nop 1
	v_cndmask_b32_e32 v32, 1.0, v35, vcc
	v_mul_f32_e32 v32, v33, v32
	v_add_u32_e32 v33, 0xa800, v144
	ds_read2_b32 v[58:59], v33 offset1:32
	s_waitcnt lgkmcnt(0)
	v_mul_f32_e32 v32, v58, v32
	ds_write_b32 v144, v34 offset:6144
	ds_write_b32 v144, v32 offset:43008
	v_add_f32_e32 v32, v61, v147
	v_mul_f32_e32 v32, 0xbfb8aa3b, v32
	v_exp_f32_e32 v32, v32
	v_add_f32_e32 v34, v45, v146
	v_mul_f32_e32 v34, 0xbfb8aa3b, v34
	v_exp_f32_e32 v34, v34
	v_add_f32_e32 v32, 1.0, v32
	v_rcp_f32_e32 v32, v32
	ds_read2_b32 v[44:45], v33 offset0:64 offset1:96
	v_add_f32_e32 v34, 1.0, v34
	v_rcp_f32_e32 v34, v34
	v_mul_f32_e32 v32, v32, v96
	v_mul_f32_e32 v35, 0x3fb8aa3b, v32
	v_add_f32_e32 v32, v32, v32
	v_mul_f32_e32 v36, 0x3fb8aa3b, v32
	v_rndne_f32_e32 v36, v36
	v_fmamk_f32 v38, v36, 0xbf317218, v32
	v_fmac_f32_e32 v38, 0x3102e308, v36
	v_fmamk_f32 v40, v38, 0x395133b1, v192
	v_cmp_eq_f32_e32 vcc, s21, v36
	v_cvt_i32_f32_e32 v36, v36
	v_fmaak_f32 v40, v38, v40, 0x3c0887f9
	v_fmaak_f32 v40, v38, v40, 0x3d2aaa81
	v_fmaak_f32 v40, v38, v40, 0x3e2aaaab
	v_fma_f32 v40, v38, v40, 0.5
	v_ldexp_f32 v36, 1.0, v36
	v_mul_f32_e32 v40, v38, v40
	v_cndmask_b32_e32 v36, v36, v202, vcc
	v_fmac_f32_e32 v38, v38, v40
	v_add_f32_e32 v40, -1.0, v36
	v_fmac_f32_e32 v40, v36, v38
	v_add_f32_e32 v36, v40, v40
	v_cndmask_b32_e32 v36, v40, v36, vcc
	v_cmp_nlt_f32_e32 vcc, s22, v32
	v_exp_f32_e32 v35, v35
	s_nop 0
	v_cndmask_b32_e64 v36, v201, -v36, vcc
	v_cmp_gt_f32_e32 vcc, s23, v36
	v_mul_f32_e32 v38, 0x4f800000, v36
	s_nop 0
	v_cndmask_b32_e32 v36, v36, v38, vcc
	v_sqrt_f32_e32 v38, v36
	s_nop 0
	v_add_u32_e32 v40, -1, v38
	v_fma_f32 v42, -v40, v38, v36
	v_cmp_ge_f32_e64 s[0:1], 0, v42
	v_add_u32_e32 v42, 1, v38
	s_nop 0
	v_cndmask_b32_e64 v40, v38, v40, s[0:1]
	v_fma_f32 v38, -v42, v38, v36
	v_cmp_lt_f32_e64 s[0:1], 0, v38
	s_nop 1
	v_cndmask_b32_e64 v38, v40, v42, s[0:1]
	v_mul_f32_e32 v40, 0x37800000, v38
	v_cndmask_b32_e32 v38, v38, v40, vcc
	v_cmp_class_f32_e32 vcc, v36, v193
	s_nop 1
	v_cndmask_b32_e32 v36, v38, v36, vcc
	v_cmp_ngt_f32_e32 vcc, s24, v32
	s_nop 1
	v_cndmask_b32_e32 v32, 1.0, v36, vcc
	v_mul_f32_e32 v32, v34, v32
	s_waitcnt lgkmcnt(0)
	v_mul_f32_e32 v32, v44, v32
	ds_write_b32 v144, v35 offset:6400
	ds_write_b32 v144, v32 offset:43264
	v_add_f32_e32 v32, v62, v147
	v_mul_f32_e32 v32, 0xbfb8aa3b, v32
	v_exp_f32_e32 v32, v32
	v_add_f32_e32 v34, v46, v146
	v_mul_f32_e32 v34, 0xbfb8aa3b, v34
	v_exp_f32_e32 v34, v34
	v_add_f32_e32 v32, 1.0, v32
	v_rcp_f32_e32 v32, v32
	v_add_f32_e32 v34, 1.0, v34
	v_rcp_f32_e32 v34, v34
	v_mul_f32_e32 v32, v32, v96
	v_mul_f32_e32 v35, 0x3fb8aa3b, v32
	v_add_f32_e32 v32, v32, v32
	v_exp_f32_e32 v36, v35
	v_mul_f32_e32 v35, 0x3fb8aa3b, v32
	v_rndne_f32_e32 v35, v35
	v_fmamk_f32 v38, v35, 0xbf317218, v32
	v_fmac_f32_e32 v38, 0x3102e308, v35
	v_fmamk_f32 v40, v38, 0x395133b1, v192
	v_cmp_eq_f32_e32 vcc, s21, v35
	v_cvt_i32_f32_e32 v35, v35
	v_fmaak_f32 v40, v38, v40, 0x3c0887f9
	v_fmaak_f32 v40, v38, v40, 0x3d2aaa81
	v_fmaak_f32 v40, v38, v40, 0x3e2aaaab
	v_fma_f32 v40, v38, v40, 0.5
	v_ldexp_f32 v35, 1.0, v35
	v_mul_f32_e32 v40, v38, v40
	v_cndmask_b32_e32 v35, v35, v202, vcc
	v_fmac_f32_e32 v38, v38, v40
	v_add_f32_e32 v40, -1.0, v35
	v_fmac_f32_e32 v40, v35, v38
	v_add_f32_e32 v35, v40, v40
	v_cndmask_b32_e32 v35, v40, v35, vcc
	v_cmp_nlt_f32_e32 vcc, s22, v32
	s_nop 1
	v_cndmask_b32_e64 v35, v201, -v35, vcc
	v_cmp_gt_f32_e32 vcc, s23, v35
	v_mul_f32_e32 v38, 0x4f800000, v35
	s_nop 0
	v_cndmask_b32_e32 v35, v35, v38, vcc
	v_sqrt_f32_e32 v38, v35
	s_nop 0
	v_add_u32_e32 v40, -1, v38
	v_fma_f32 v42, -v40, v38, v35
	v_cmp_ge_f32_e64 s[0:1], 0, v42
	v_add_u32_e32 v42, 1, v38
	s_nop 0
	v_cndmask_b32_e64 v40, v38, v40, s[0:1]
	v_fma_f32 v38, -v42, v38, v35
	v_cmp_lt_f32_e64 s[0:1], 0, v38
	s_nop 1
	v_cndmask_b32_e64 v38, v40, v42, s[0:1]
	v_mul_f32_e32 v40, 0x37800000, v38
	v_cndmask_b32_e32 v38, v38, v40, vcc
	v_cmp_class_f32_e32 vcc, v35, v193
	s_nop 1
	v_cndmask_b32_e32 v35, v38, v35, vcc
	v_cmp_ngt_f32_e32 vcc, s24, v32
	s_nop 1
	v_cndmask_b32_e32 v32, 1.0, v35, vcc
	v_mul_f32_e32 v32, v34, v32
	ds_read2_b32 v[34:35], v33 offset0:128 offset1:160
	s_waitcnt lgkmcnt(0)
	v_mul_f32_e32 v32, v34, v32
	ds_write_b32 v144, v36 offset:6656
	ds_write_b32 v144, v32 offset:43520
	v_add_f32_e32 v32, v63, v147
	v_mul_f32_e32 v32, 0xbfb8aa3b, v32
	v_exp_f32_e32 v32, v32
	v_add_f32_e32 v34, v47, v146
	v_mul_f32_e32 v34, 0xbfb8aa3b, v34
	v_exp_f32_e32 v34, v34
	v_add_f32_e32 v32, 1.0, v32
	v_rcp_f32_e32 v32, v32
	v_add_f32_e32 v34, 1.0, v34
	v_rcp_f32_e32 v36, v34
	v_mul_f32_e32 v32, v32, v96
	v_mul_f32_e32 v34, 0x3fb8aa3b, v32
	v_add_f32_e32 v32, v32, v32
	v_mul_f32_e32 v38, 0x3fb8aa3b, v32
	v_rndne_f32_e32 v38, v38
	v_fmamk_f32 v40, v38, 0xbf317218, v32
	v_fmac_f32_e32 v40, 0x3102e308, v38
	v_fmamk_f32 v42, v40, 0x395133b1, v192
	v_cmp_eq_f32_e32 vcc, s21, v38
	v_cvt_i32_f32_e32 v38, v38
	v_fmaak_f32 v42, v40, v42, 0x3c0887f9
	v_fmaak_f32 v42, v40, v42, 0x3d2aaa81
	v_fmaak_f32 v42, v40, v42, 0x3e2aaaab
	v_fma_f32 v42, v40, v42, 0.5
	v_ldexp_f32 v38, 1.0, v38
	v_mul_f32_e32 v42, v40, v42
	v_cndmask_b32_e32 v38, v38, v202, vcc
	v_fmac_f32_e32 v40, v40, v42
	v_add_f32_e32 v42, -1.0, v38
	v_fmac_f32_e32 v42, v38, v40
	v_add_f32_e32 v38, v42, v42
	v_cndmask_b32_e32 v38, v42, v38, vcc
	v_cmp_nlt_f32_e32 vcc, s22, v32
	v_add_u32_e32 v96, s3, v145
	v_lshlrev_b64 v[46:47], 2, v[96:97]
	v_cndmask_b32_e64 v38, v201, -v38, vcc
	v_cmp_gt_f32_e32 vcc, s23, v38
	v_mul_f32_e32 v40, 0x4f800000, v38
	v_lshl_add_u64 v[60:61], s[18:19], 0, v[46:47]
	v_cndmask_b32_e32 v38, v38, v40, vcc
	v_sqrt_f32_e32 v40, v38
	v_exp_f32_e32 v34, v34
	s_movk_i32 s18, 0x1600
	s_mov_b32 s19, 0x2c000
	v_add_u32_e32 v42, -1, v40
	v_fma_f32 v44, -v42, v40, v38
	v_cmp_ge_f32_e64 s[0:1], 0, v44
	v_add_u32_e32 v44, 1, v40
	s_nop 0
	v_cndmask_b32_e64 v42, v40, v42, s[0:1]
	v_fma_f32 v40, -v44, v40, v38
	v_cmp_lt_f32_e64 s[0:1], 0, v40
	s_nop 1
	v_cndmask_b32_e64 v40, v42, v44, s[0:1]
	v_mul_f32_e32 v42, 0x37800000, v40
	v_cndmask_b32_e32 v40, v40, v42, vcc
	v_cmp_class_f32_e32 vcc, v38, v193
	s_nop 1
	v_cndmask_b32_e32 v38, v40, v38, vcc
	v_cmp_ngt_f32_e32 vcc, s24, v32
	s_nop 1
	v_cndmask_b32_e32 v32, 1.0, v38, vcc
	v_mul_f32_e32 v36, v36, v32
	ds_read2_b32 v[32:33], v33 offset0:192 offset1:224
	s_waitcnt lgkmcnt(0)
	v_mul_f32_e32 v32, v32, v36
	ds_write_b32 v144, v32 offset:43776
	v_mov_b32_e32 v32, v226
	s_waitcnt vmcnt(0)
	v_mul_f32_e32 v32, 0xbfb8aa3b, v32
	v_exp_f32_e32 v32, v32
	s_nop 0
	v_add_f32_e32 v36, 1.0, v32
	v_add_f32_e32 v38, -1.0, v36
	v_sub_f32_e32 v40, v38, v36
	v_add_f32_e32 v40, 1.0, v40
	v_sub_f32_e32 v38, v32, v38
	v_add_f32_e32 v38, v38, v40
	v_frexp_mant_f32_e32 v40, v36
	v_cvt_f64_f32_e32 v[60:61], v36
	v_cmp_gt_f32_e32 vcc, s8, v40
	v_frexp_exp_i32_f64_e32 v40, v[60:61]
	s_nop 0
	v_subbrev_co_u32_e32 v40, vcc, 0, v40, vcc
	v_sub_u32_e32 v42, 0, v40
	v_ldexp_f32 v36, v36, v42
	v_ldexp_f32 v38, v38, v42
	v_add_f32_e32 v42, -1.0, v36
	v_add_f32_e32 v48, 1.0, v36
	v_add_f32_e32 v44, 1.0, v42
	v_add_f32_e32 v50, -1.0, v48
	v_sub_f32_e32 v44, v36, v44
	v_sub_f32_e32 v36, v36, v50
	v_add_f32_e32 v36, v38, v36
	v_add_f32_e32 v44, v38, v44
	v_add_f32_e32 v38, v48, v36
	v_sub_f32_e32 v48, v38, v48
	v_sub_f32_e32 v36, v36, v48
	v_rcp_f32_e32 v48, v38
	v_add_f32_e32 v61, v42, v44
	v_sub_f32_e32 v42, v61, v42
	v_sub_f32_e32 v42, v44, v42
	v_mul_f32_e32 v44, v61, v48
	v_mul_f32_e32 v62, v38, v44
	v_fma_f32 v146, v44, v38, -v62
	v_fmac_f32_e32 v146, v44, v36
	v_add_f32_e32 v60, v62, v146
	v_sub_f32_e32 v63, v61, v60
	v_pk_add_f32 v[148:149], v[60:61], v[62:63] neg_lo:[0,1] neg_hi:[0,1]
	v_mov_b32_e32 v147, v60
	v_pk_add_f32 v[60:61], v[148:149], v[146:147] neg_lo:[0,1] neg_hi:[0,1]
	v_cmp_neq_f32_e32 vcc, s10, v32
	v_add_f32_e32 v42, v42, v61
	v_add_f32_e32 v42, v60, v42
	v_add_f32_e32 v61, v63, v42
	v_mul_f32_e32 v50, v48, v61
	v_mul_f32_e32 v62, v38, v50
	v_fma_f32 v146, v50, v38, -v62
	v_fmac_f32_e32 v146, v50, v36
	v_add_f32_e32 v60, v62, v146
	v_sub_f32_e32 v36, v63, v61
	v_sub_f32_e32 v63, v61, v60
	v_pk_add_f32 v[148:149], v[60:61], v[62:63] neg_lo:[0,1] neg_hi:[0,1]
	v_mov_b32_e32 v147, v60
	v_add_f32_e32 v36, v42, v36
	v_pk_add_f32 v[60:61], v[148:149], v[146:147] neg_lo:[0,1] neg_hi:[0,1]
	v_add_f32_e32 v38, v44, v50
	v_add_f32_e32 v36, v36, v61
	v_add_f32_e32 v36, v60, v36
	v_add_f32_e32 v36, v63, v36
	v_sub_f32_e32 v42, v38, v44
	v_mul_f32_e32 v36, v48, v36
	v_sub_f32_e32 v42, v50, v42
	v_add_f32_e32 v36, v42, v36
	v_add_f32_e32 v42, v38, v36
	v_cvt_f32_i32_e32 v60, v40
	v_mul_f32_e32 v44, v42, v42
	v_fmamk_f32 v48, v44, 0x3e9b6dac, v191
	v_fmaak_f32 v169, v44, v48, 0x3f2aaada
	v_mul_f32_e32 v61, v42, v44
	v_pk_mul_f32 v[146:147], v[60:61], v[168:169]
	v_ldexp_f32 v63, v42, 1
	v_fma_f32 v62, v60, s9, -v146
	v_fmac_f32_e32 v62, 0xb102e308, v60
	v_sub_f32_e32 v38, v42, v38
	v_pk_add_f32 v[60:61], v[146:147], v[62:63]
	v_sub_f32_e32 v36, v36, v38
	v_sub_f32_e32 v38, v61, v63
	v_ldexp_f32 v36, v36, 1
	v_sub_f32_e32 v38, v147, v38
	v_add_f32_e32 v149, v36, v38
	v_mov_b32_e32 v148, v146
	v_pk_add_f32 v[146:147], v[60:61], v[146:147] neg_lo:[0,1] neg_hi:[0,1]
	v_pk_add_f32 v[150:151], v[60:61], v[148:149]
	v_mov_b32_e32 v63, v60
	v_mov_b32_e32 v147, v151
	v_pk_add_f32 v[152:153], v[62:63], v[146:147] neg_lo:[0,1] neg_hi:[0,1]
	v_pk_add_f32 v[62:63], v[62:63], v[146:147]
	v_mov_b32_e32 v148, v149
	v_pk_add_f32 v[146:147], v[62:63], v[60:61] op_sel:[1,0] op_sel_hi:[0,1] neg_lo:[0,1] neg_hi:[0,1]
	v_pk_add_f32 v[154:155], v[150:151], v[146:147] op_sel_hi:[1,0] neg_lo:[0,1] neg_hi:[0,1]
	v_mov_b32_e32 v150, v151
	v_mov_b32_e32 v151, v63
	v_pk_mov_b32 v[146:147], v[60:61], v[146:147] op_sel:[1,0]
	v_mov_b32_e32 v149, v60
	v_pk_add_f32 v[146:147], v[150:151], v[146:147] neg_lo:[0,1] neg_hi:[0,1]
	v_mov_b32_e32 v154, v152
	v_pk_add_f32 v[60:61], v[148:149], v[146:147] neg_lo:[0,1] neg_hi:[0,1]
	v_mov_b32_e32 v153, v63
	v_pk_add_f32 v[146:147], v[154:155], v[60:61]
	v_readlane_b32 s10, v248, 33
	v_pk_add_f32 v[148:149], v[146:147], v[146:147] op_sel:[0,1] op_sel_hi:[1,0]
	v_pk_add_f32 v[62:63], v[62:63], v[148:149] op_sel:[1,0] op_sel_hi:[0,1]
	v_mov_b32_e32 v147, v62
	v_pk_add_f32 v[150:151], v[146:147], v[152:153] neg_lo:[0,1] neg_hi:[0,1]
	v_mov_b32_e32 v61, v148
	v_sub_f32_e32 v36, v146, v150
	v_pk_add_f32 v[60:61], v[60:61], v[150:151] neg_lo:[0,1] neg_hi:[0,1]
	v_sub_f32_e32 v36, v152, v36
	v_add_f32_e32 v36, v60, v36
	v_add_f32_e32 v36, v36, v61
	v_add_f32_e32 v36, v62, v36
	v_cndmask_b32_e32 v36, v199, v36, vcc
	v_cmp_ngt_f32_e32 vcc, -1.0, v32
	v_lshl_add_u64 v[60:61], s[52:53], 0, v[46:47]
	v_lshl_add_u64 v[46:47], s[16:17], 0, v[46:47]
	v_cndmask_b32_e32 v36, v200, v36, vcc
	v_cmp_neq_f32_e32 vcc, -1.0, v32
	v_mov_b32_e32 v38, v227
	s_mov_b64 s[16:17], s[82:83]
	v_cndmask_b32_e32 v36, v201, v36, vcc
	v_cmp_lt_f32_e64 vcc, |v32|, s20
	s_mov_b32 s20, 0x58000
	s_waitcnt vmcnt(0)
	v_add_f32_e32 v0, v0, v38
	v_cndmask_b32_e32 v32, v36, v32, vcc
	v_mov_b32_e32 v36, v228
	v_mul_f32_e32 v32, 0xc1000000, v32
	v_mul_f32_e32 v0, 0xbfb8aa3b, v0
	v_exp_f32_e32 v0, v0
	v_add_f32_e32 v1, v1, v38
	v_mul_f32_e32 v1, 0xbfb8aa3b, v1
	v_exp_f32_e32 v1, v1
	v_add_f32_e32 v0, 1.0, v0
	v_rcp_f32_e32 v0, v0
	v_add_f32_e32 v1, 1.0, v1
	v_rcp_f32_e32 v1, v1
	s_waitcnt vmcnt(0)
	v_add_f32_e32 v16, v16, v36
	v_mul_f32_e32 v16, 0xbfb8aa3b, v16
	v_exp_f32_e32 v16, v16
	s_nop 0
	v_add_f32_e32 v16, 1.0, v16
	v_rcp_f32_e32 v16, v16
	s_nop 0
	v_mul_f32_e32 v16, v16, v32
	v_mul_f32_e32 v40, 0x3fb8aa3b, v16
	v_add_f32_e32 v16, v16, v16
	v_mul_f32_e32 v42, 0x3fb8aa3b, v16
	v_rndne_f32_e32 v42, v42
	v_fmamk_f32 v44, v42, 0xbf317218, v16
	v_fmac_f32_e32 v44, 0x3102e308, v42
	v_fmamk_f32 v46, v44, 0x395133b1, v192
	v_cmp_eq_f32_e32 vcc, s21, v42
	v_cvt_i32_f32_e32 v42, v42
	v_fmaak_f32 v46, v44, v46, 0x3c0887f9
	v_fmaak_f32 v46, v44, v46, 0x3d2aaa81
	v_fmaak_f32 v46, v44, v46, 0x3e2aaaab
	v_fma_f32 v46, v44, v46, 0.5
	v_ldexp_f32 v42, 1.0, v42
	v_mul_f32_e32 v46, v44, v46
	v_cndmask_b32_e32 v42, v42, v202, vcc
	v_fmac_f32_e32 v44, v44, v46
	v_add_f32_e32 v46, -1.0, v42
	v_fmac_f32_e32 v46, v42, v44
	v_add_f32_e32 v42, v46, v46
	v_cndmask_b32_e32 v42, v46, v42, vcc
	v_cmp_nlt_f32_e32 vcc, s22, v16
	v_exp_f32_e32 v40, v40
	s_nop 0
	v_cndmask_b32_e64 v42, v201, -v42, vcc
	v_cmp_gt_f32_e32 vcc, s23, v42
	v_mul_f32_e32 v44, 0x4f800000, v42
	s_nop 0
	v_cndmask_b32_e32 v42, v42, v44, vcc
	v_sqrt_f32_e32 v44, v42
	s_nop 0
	v_add_u32_e32 v46, -1, v44
	v_fma_f32 v47, -v46, v44, v42
	v_cmp_ge_f32_e64 s[0:1], 0, v47
	v_add_u32_e32 v47, 1, v44
	s_nop 0
	v_cndmask_b32_e64 v46, v44, v46, s[0:1]
	v_fma_f32 v44, -v47, v44, v42
	v_cmp_lt_f32_e64 s[0:1], 0, v44
	s_nop 1
	v_cndmask_b32_e64 v44, v46, v47, s[0:1]
	v_mul_f32_e32 v46, 0x37800000, v44
	v_cndmask_b32_e32 v44, v44, v46, vcc
	v_cmp_class_f32_e32 vcc, v42, v193
	s_nop 1
	v_cndmask_b32_e32 v42, v44, v42, vcc
	v_cmp_ngt_f32_e32 vcc, s24, v16
	s_nop 1
	v_cndmask_b32_e32 v16, 1.0, v42, vcc
	v_mul_f32_e32 v0, v0, v16
	v_mul_f32_e32 v0, v135, v0
	ds_write_b32 v144, v40 offset:128
	ds_write_b32 v144, v0 offset:36992
	v_add_f32_e32 v0, v17, v36
	v_mul_f32_e32 v0, 0xbfb8aa3b, v0
	v_exp_f32_e32 v0, v0
	s_nop 0
	v_add_f32_e32 v0, 1.0, v0
	v_rcp_f32_e32 v0, v0
	s_nop 0
	v_mul_f32_e32 v0, v0, v32
	v_mul_f32_e32 v16, 0x3fb8aa3b, v0
	v_add_f32_e32 v0, v0, v0
	v_mul_f32_e32 v17, 0x3fb8aa3b, v0
	v_rndne_f32_e32 v17, v17
	v_fmamk_f32 v40, v17, 0xbf317218, v0
	v_fmac_f32_e32 v40, 0x3102e308, v17
	v_fmamk_f32 v42, v40, 0x395133b1, v192
	v_cmp_eq_f32_e32 vcc, s21, v17
	v_cvt_i32_f32_e32 v17, v17
	v_fmaak_f32 v42, v40, v42, 0x3c0887f9
	v_fmaak_f32 v42, v40, v42, 0x3d2aaa81
	v_fmaak_f32 v42, v40, v42, 0x3e2aaaab
	v_fma_f32 v42, v40, v42, 0.5
	v_ldexp_f32 v17, 1.0, v17
	v_mul_f32_e32 v42, v40, v42
	v_cndmask_b32_e32 v17, v17, v202, vcc
	v_fmac_f32_e32 v40, v40, v42
	v_add_f32_e32 v42, -1.0, v17
	v_fmac_f32_e32 v42, v17, v40
	v_add_f32_e32 v17, v42, v42
	v_cndmask_b32_e32 v17, v42, v17, vcc
	v_cmp_nlt_f32_e32 vcc, s22, v0
	v_exp_f32_e32 v16, v16
	s_nop 0
	v_cndmask_b32_e64 v17, v201, -v17, vcc
	v_cmp_gt_f32_e32 vcc, s23, v17
	v_mul_f32_e32 v40, 0x4f800000, v17
	s_nop 0
	v_cndmask_b32_e32 v17, v17, v40, vcc
	v_sqrt_f32_e32 v40, v17
	s_nop 0
	v_add_u32_e32 v42, -1, v40
	v_fma_f32 v44, -v42, v40, v17
	v_cmp_ge_f32_e64 s[0:1], 0, v44
	v_add_u32_e32 v44, 1, v40
	s_nop 0
	v_cndmask_b32_e64 v42, v40, v42, s[0:1]
	v_fma_f32 v40, -v44, v40, v17
	v_cmp_lt_f32_e64 s[0:1], 0, v40
	s_nop 1
	v_cndmask_b32_e64 v40, v42, v44, s[0:1]
	v_mul_f32_e32 v42, 0x37800000, v40
	v_cndmask_b32_e32 v40, v40, v42, vcc
	v_cmp_class_f32_e32 vcc, v17, v193
	s_nop 1
	v_cndmask_b32_e32 v17, v40, v17, vcc
	v_cmp_ngt_f32_e32 vcc, s24, v0
	s_nop 1
	v_cndmask_b32_e32 v0, 1.0, v17, vcc
	v_mul_f32_e32 v0, v1, v0
	v_mul_f32_e32 v0, v49, v0
	ds_write_b32 v144, v16 offset:384
	ds_write_b32 v144, v0 offset:37248
	v_add_f32_e32 v0, v18, v36
	v_mul_f32_e32 v0, 0xbfb8aa3b, v0
	v_exp_f32_e32 v0, v0
	v_add_f32_e32 v1, v2, v38
	v_mul_f32_e32 v1, 0xbfb8aa3b, v1
	v_exp_f32_e32 v1, v1
	v_add_f32_e32 v0, 1.0, v0
	v_rcp_f32_e32 v0, v0
	v_add_f32_e32 v1, 1.0, v1
	v_rcp_f32_e32 v1, v1
	v_mul_f32_e32 v0, v0, v32
	v_mul_f32_e32 v2, 0x3fb8aa3b, v0
	v_add_f32_e32 v0, v0, v0
	v_mul_f32_e32 v16, 0x3fb8aa3b, v0
	v_rndne_f32_e32 v16, v16
	v_fmamk_f32 v17, v16, 0xbf317218, v0
	v_fmac_f32_e32 v17, 0x3102e308, v16
	v_fmamk_f32 v18, v17, 0x395133b1, v192
	v_cmp_eq_f32_e32 vcc, s21, v16
	v_cvt_i32_f32_e32 v16, v16
	v_fmaak_f32 v18, v17, v18, 0x3c0887f9
	v_fmaak_f32 v18, v17, v18, 0x3d2aaa81
	v_fmaak_f32 v18, v17, v18, 0x3e2aaaab
	v_fma_f32 v18, v17, v18, 0.5
	v_ldexp_f32 v16, 1.0, v16
	v_mul_f32_e32 v18, v17, v18
	v_cndmask_b32_e32 v16, v16, v202, vcc
	v_fmac_f32_e32 v17, v17, v18
	v_add_f32_e32 v18, -1.0, v16
	v_fmac_f32_e32 v18, v16, v17
	v_add_f32_e32 v16, v18, v18
	v_cndmask_b32_e32 v16, v18, v16, vcc
	v_cmp_nlt_f32_e32 vcc, s22, v0
	v_exp_f32_e32 v2, v2
	s_nop 0
	v_cndmask_b32_e64 v16, v201, -v16, vcc
	v_cmp_gt_f32_e32 vcc, s23, v16
	v_mul_f32_e32 v17, 0x4f800000, v16
	s_nop 0
	v_cndmask_b32_e32 v16, v16, v17, vcc
	v_sqrt_f32_e32 v17, v16
	s_nop 0
	v_add_u32_e32 v18, -1, v17
	v_fma_f32 v40, -v18, v17, v16
	v_cmp_ge_f32_e64 s[0:1], 0, v40
	v_add_u32_e32 v40, 1, v17
	s_nop 0
	v_cndmask_b32_e64 v18, v17, v18, s[0:1]
	v_fma_f32 v17, -v40, v17, v16
	v_cmp_lt_f32_e64 s[0:1], 0, v17
	s_nop 1
	v_cndmask_b32_e64 v17, v18, v40, s[0:1]
	v_mul_f32_e32 v18, 0x37800000, v17
	v_cndmask_b32_e32 v17, v17, v18, vcc
	v_cmp_class_f32_e32 vcc, v16, v193
	s_nop 1
	v_cndmask_b32_e32 v16, v17, v16, vcc
	v_cmp_ngt_f32_e32 vcc, s24, v0
	s_nop 1
	v_cndmask_b32_e32 v0, 1.0, v16, vcc
	v_mul_f32_e32 v0, v1, v0
	v_mul_f32_e32 v0, v137, v0
	ds_write_b32 v144, v2 offset:640
	ds_write_b32 v144, v0 offset:37504
	v_add_f32_e32 v0, v19, v36
	v_mul_f32_e32 v0, 0xbfb8aa3b, v0
	v_exp_f32_e32 v0, v0
	v_add_f32_e32 v1, v3, v38
	v_mul_f32_e32 v1, 0xbfb8aa3b, v1
	v_exp_f32_e32 v1, v1
	v_add_f32_e32 v0, 1.0, v0
	v_rcp_f32_e32 v0, v0
	v_add_f32_e32 v1, 1.0, v1
	v_rcp_f32_e32 v1, v1
	v_mul_f32_e32 v0, v0, v32
	v_mul_f32_e32 v2, 0x3fb8aa3b, v0
	v_add_f32_e32 v0, v0, v0
	v_mul_f32_e32 v3, 0x3fb8aa3b, v0
	v_rndne_f32_e32 v3, v3
	v_fmamk_f32 v16, v3, 0xbf317218, v0
	v_fmac_f32_e32 v16, 0x3102e308, v3
	v_fmamk_f32 v17, v16, 0x395133b1, v192
	v_cmp_eq_f32_e32 vcc, s21, v3
	v_cvt_i32_f32_e32 v3, v3
	v_fmaak_f32 v17, v16, v17, 0x3c0887f9
	v_fmaak_f32 v17, v16, v17, 0x3d2aaa81
	v_fmaak_f32 v17, v16, v17, 0x3e2aaaab
	v_fma_f32 v17, v16, v17, 0.5
	v_ldexp_f32 v3, 1.0, v3
	v_mul_f32_e32 v17, v16, v17
	v_cndmask_b32_e32 v3, v3, v202, vcc
	v_fmac_f32_e32 v16, v16, v17
	v_add_f32_e32 v17, -1.0, v3
	v_fmac_f32_e32 v17, v3, v16
	v_add_f32_e32 v3, v17, v17
	v_cndmask_b32_e32 v3, v17, v3, vcc
	v_cmp_nlt_f32_e32 vcc, s22, v0
	v_exp_f32_e32 v2, v2
	s_nop 0
	v_cndmask_b32_e64 v3, v201, -v3, vcc
	v_cmp_gt_f32_e32 vcc, s23, v3
	v_mul_f32_e32 v16, 0x4f800000, v3
	s_nop 0
	v_cndmask_b32_e32 v3, v3, v16, vcc
	v_sqrt_f32_e32 v16, v3
	s_nop 0
	v_add_u32_e32 v17, -1, v16
	v_fma_f32 v18, -v17, v16, v3
	v_cmp_ge_f32_e64 s[0:1], 0, v18
	v_add_u32_e32 v18, 1, v16
	s_nop 0
	v_cndmask_b32_e64 v17, v16, v17, s[0:1]
	v_fma_f32 v16, -v18, v16, v3
	v_cmp_lt_f32_e64 s[0:1], 0, v16
	s_nop 1
	v_cndmask_b32_e64 v16, v17, v18, s[0:1]
	v_mul_f32_e32 v17, 0x37800000, v16
	v_cndmask_b32_e32 v16, v16, v17, vcc
	v_cmp_class_f32_e32 vcc, v3, v193
	s_nop 1
	v_cndmask_b32_e32 v3, v16, v3, vcc
	v_cmp_ngt_f32_e32 vcc, s24, v0
	s_nop 1
	v_cndmask_b32_e32 v0, 1.0, v3, vcc
	v_mul_f32_e32 v0, v1, v0
	v_mul_f32_e32 v0, v51, v0
	ds_write_b32 v144, v2 offset:896
	ds_write_b32 v144, v0 offset:37760
	v_add_f32_e32 v0, v20, v36
	v_mul_f32_e32 v0, 0xbfb8aa3b, v0
	v_exp_f32_e32 v0, v0
	v_add_f32_e32 v1, v4, v38
	v_mul_f32_e32 v1, 0xbfb8aa3b, v1
	v_exp_f32_e32 v1, v1
	v_add_f32_e32 v0, 1.0, v0
	v_rcp_f32_e32 v0, v0
	v_add_f32_e32 v1, 1.0, v1
	v_rcp_f32_e32 v1, v1
	v_mul_f32_e32 v0, v0, v32
	v_mul_f32_e32 v2, 0x3fb8aa3b, v0
	v_add_f32_e32 v0, v0, v0
	v_mul_f32_e32 v3, 0x3fb8aa3b, v0
	v_rndne_f32_e32 v3, v3
	v_fmamk_f32 v4, v3, 0xbf317218, v0
	v_fmac_f32_e32 v4, 0x3102e308, v3
	v_fmamk_f32 v16, v4, 0x395133b1, v192
	v_cmp_eq_f32_e32 vcc, s21, v3
	v_cvt_i32_f32_e32 v3, v3
	v_fmaak_f32 v16, v4, v16, 0x3c0887f9
	v_fmaak_f32 v16, v4, v16, 0x3d2aaa81
	v_fmaak_f32 v16, v4, v16, 0x3e2aaaab
	v_fma_f32 v16, v4, v16, 0.5
	v_ldexp_f32 v3, 1.0, v3
	v_mul_f32_e32 v16, v4, v16
	v_cndmask_b32_e32 v3, v3, v202, vcc
	v_fmac_f32_e32 v4, v4, v16
	v_add_f32_e32 v16, -1.0, v3
	v_fmac_f32_e32 v16, v3, v4
	v_add_f32_e32 v3, v16, v16
	v_cndmask_b32_e32 v3, v16, v3, vcc
	v_cmp_nlt_f32_e32 vcc, s22, v0
	v_exp_f32_e32 v2, v2
	s_nop 0
	v_cndmask_b32_e64 v3, v201, -v3, vcc
	v_cmp_gt_f32_e32 vcc, s23, v3
	v_mul_f32_e32 v4, 0x4f800000, v3
	s_nop 0
	v_cndmask_b32_e32 v3, v3, v4, vcc
	v_sqrt_f32_e32 v4, v3
	s_nop 0
	v_add_u32_e32 v16, -1, v4
	v_fma_f32 v17, -v16, v4, v3
	v_cmp_ge_f32_e64 s[0:1], 0, v17
	v_add_u32_e32 v17, 1, v4
	s_nop 0
	v_cndmask_b32_e64 v16, v4, v16, s[0:1]
	v_fma_f32 v4, -v17, v4, v3
	v_cmp_lt_f32_e64 s[0:1], 0, v4
	s_nop 1
	v_cndmask_b32_e64 v4, v16, v17, s[0:1]
	v_mul_f32_e32 v16, 0x37800000, v4
	v_cndmask_b32_e32 v4, v4, v16, vcc
	v_cmp_class_f32_e32 vcc, v3, v193
	s_nop 1
	v_cndmask_b32_e32 v3, v4, v3, vcc
	v_cmp_ngt_f32_e32 vcc, s24, v0
	s_nop 1
	v_cndmask_b32_e32 v0, 1.0, v3, vcc
	v_mul_f32_e32 v0, v1, v0
	v_mul_f32_e32 v0, v139, v0
	ds_write_b32 v144, v2 offset:2176
	ds_write_b32 v144, v0 offset:39040
	v_add_f32_e32 v0, v21, v36
	v_mul_f32_e32 v0, 0xbfb8aa3b, v0
	v_exp_f32_e32 v0, v0
	v_add_f32_e32 v1, v5, v38
	v_mul_f32_e32 v1, 0xbfb8aa3b, v1
	v_exp_f32_e32 v1, v1
	v_add_f32_e32 v0, 1.0, v0
	v_rcp_f32_e32 v0, v0
	v_add_f32_e32 v1, 1.0, v1
	v_rcp_f32_e32 v1, v1
	v_mul_f32_e32 v0, v0, v32
	v_mul_f32_e32 v2, 0x3fb8aa3b, v0
	v_add_f32_e32 v0, v0, v0
	v_mul_f32_e32 v3, 0x3fb8aa3b, v0
	v_rndne_f32_e32 v3, v3
	v_fmamk_f32 v4, v3, 0xbf317218, v0
	v_fmac_f32_e32 v4, 0x3102e308, v3
	v_fmamk_f32 v5, v4, 0x395133b1, v192
	v_cmp_eq_f32_e32 vcc, s21, v3
	v_cvt_i32_f32_e32 v3, v3
	v_fmaak_f32 v5, v4, v5, 0x3c0887f9
	v_fmaak_f32 v5, v4, v5, 0x3d2aaa81
	v_fmaak_f32 v5, v4, v5, 0x3e2aaaab
	v_fma_f32 v5, v4, v5, 0.5
	v_ldexp_f32 v3, 1.0, v3
	v_mul_f32_e32 v5, v4, v5
	v_cndmask_b32_e32 v3, v3, v202, vcc
	v_fmac_f32_e32 v4, v4, v5
	v_add_f32_e32 v5, -1.0, v3
	v_fmac_f32_e32 v5, v3, v4
	v_add_f32_e32 v3, v5, v5
	v_cndmask_b32_e32 v3, v5, v3, vcc
	v_cmp_nlt_f32_e32 vcc, s22, v0
	v_exp_f32_e32 v2, v2
	s_nop 0
	v_cndmask_b32_e64 v3, v201, -v3, vcc
	v_cmp_gt_f32_e32 vcc, s23, v3
	v_mul_f32_e32 v4, 0x4f800000, v3
	s_nop 0
	v_cndmask_b32_e32 v3, v3, v4, vcc
	v_sqrt_f32_e32 v4, v3
	s_nop 0
	v_add_u32_e32 v5, -1, v4
	v_fma_f32 v16, -v5, v4, v3
	v_cmp_ge_f32_e64 s[0:1], 0, v16
	v_add_u32_e32 v16, 1, v4
	s_nop 0
	v_cndmask_b32_e64 v5, v4, v5, s[0:1]
	v_fma_f32 v4, -v16, v4, v3
	v_cmp_lt_f32_e64 s[0:1], 0, v4
	s_nop 1
	v_cndmask_b32_e64 v4, v5, v16, s[0:1]
	v_mul_f32_e32 v5, 0x37800000, v4
	v_cndmask_b32_e32 v4, v4, v5, vcc
	v_cmp_class_f32_e32 vcc, v3, v193
	s_nop 1
	v_cndmask_b32_e32 v3, v4, v3, vcc
	v_cmp_ngt_f32_e32 vcc, s24, v0
	s_nop 1
	v_cndmask_b32_e32 v0, 1.0, v3, vcc
	v_mul_f32_e32 v0, v1, v0
	v_mul_f32_e32 v0, v37, v0
	ds_write_b32 v144, v2 offset:2432
	ds_write_b32 v144, v0 offset:39296
	v_add_f32_e32 v0, v22, v36
	v_mul_f32_e32 v0, 0xbfb8aa3b, v0
	v_exp_f32_e32 v0, v0
	v_add_f32_e32 v1, v6, v38
	v_mul_f32_e32 v1, 0xbfb8aa3b, v1
	v_exp_f32_e32 v1, v1
	v_add_f32_e32 v0, 1.0, v0
	v_rcp_f32_e32 v0, v0
	v_add_f32_e32 v1, 1.0, v1
	v_rcp_f32_e32 v1, v1
	v_mul_f32_e32 v0, v0, v32
	v_mul_f32_e32 v2, 0x3fb8aa3b, v0
	v_add_f32_e32 v0, v0, v0
	v_mul_f32_e32 v3, 0x3fb8aa3b, v0
	v_rndne_f32_e32 v3, v3
	v_fmamk_f32 v4, v3, 0xbf317218, v0
	v_fmac_f32_e32 v4, 0x3102e308, v3
	v_fmamk_f32 v5, v4, 0x395133b1, v192
	v_cmp_eq_f32_e32 vcc, s21, v3
	v_cvt_i32_f32_e32 v3, v3
	v_fmaak_f32 v5, v4, v5, 0x3c0887f9
	v_fmaak_f32 v5, v4, v5, 0x3d2aaa81
	v_fmaak_f32 v5, v4, v5, 0x3e2aaaab
	v_fma_f32 v5, v4, v5, 0.5
	v_ldexp_f32 v3, 1.0, v3
	v_mul_f32_e32 v5, v4, v5
	v_cndmask_b32_e32 v3, v3, v202, vcc
	v_fmac_f32_e32 v4, v4, v5
	v_add_f32_e32 v5, -1.0, v3
	v_fmac_f32_e32 v5, v3, v4
	v_add_f32_e32 v3, v5, v5
	v_cndmask_b32_e32 v3, v5, v3, vcc
	v_cmp_nlt_f32_e32 vcc, s22, v0
	v_exp_f32_e32 v2, v2
	s_nop 0
	v_cndmask_b32_e64 v3, v201, -v3, vcc
	v_cmp_gt_f32_e32 vcc, s23, v3
	v_mul_f32_e32 v4, 0x4f800000, v3
	s_nop 0
	v_cndmask_b32_e32 v3, v3, v4, vcc
	v_sqrt_f32_e32 v4, v3
	s_nop 0
	v_add_u32_e32 v5, -1, v4
	v_fma_f32 v6, -v5, v4, v3
	v_cmp_ge_f32_e64 s[0:1], 0, v6
	v_add_u32_e32 v6, 1, v4
	s_nop 0
	v_cndmask_b32_e64 v5, v4, v5, s[0:1]
	v_fma_f32 v4, -v6, v4, v3
	v_cmp_lt_f32_e64 s[0:1], 0, v4
	s_nop 1
	v_cndmask_b32_e64 v4, v5, v6, s[0:1]
	v_mul_f32_e32 v5, 0x37800000, v4
	v_cndmask_b32_e32 v4, v4, v5, vcc
	v_cmp_class_f32_e32 vcc, v3, v193
	s_nop 1
	v_cndmask_b32_e32 v3, v4, v3, vcc
	v_cmp_ngt_f32_e32 vcc, s24, v0
	s_nop 1
	v_cndmask_b32_e32 v0, 1.0, v3, vcc
	v_mul_f32_e32 v0, v1, v0
	v_mul_f32_e32 v0, v53, v0
	ds_write_b32 v144, v2 offset:2688
	ds_write_b32 v144, v0 offset:39552
	v_add_f32_e32 v0, v23, v36
	v_mul_f32_e32 v0, 0xbfb8aa3b, v0
	v_exp_f32_e32 v0, v0
	v_add_f32_e32 v1, v7, v38
	v_mul_f32_e32 v1, 0xbfb8aa3b, v1
	v_exp_f32_e32 v1, v1
	v_add_f32_e32 v0, 1.0, v0
	v_rcp_f32_e32 v0, v0
	v_add_f32_e32 v1, 1.0, v1
	v_rcp_f32_e32 v1, v1
	v_mul_f32_e32 v0, v0, v32
	v_mul_f32_e32 v2, 0x3fb8aa3b, v0
	v_add_f32_e32 v0, v0, v0
	v_mul_f32_e32 v3, 0x3fb8aa3b, v0
	v_rndne_f32_e32 v3, v3
	v_fmamk_f32 v4, v3, 0xbf317218, v0
	v_fmac_f32_e32 v4, 0x3102e308, v3
	v_fmamk_f32 v5, v4, 0x395133b1, v192
	v_cmp_eq_f32_e32 vcc, s21, v3
	v_cvt_i32_f32_e32 v3, v3
	v_fmaak_f32 v5, v4, v5, 0x3c0887f9
	v_fmaak_f32 v5, v4, v5, 0x3d2aaa81
	v_fmaak_f32 v5, v4, v5, 0x3e2aaaab
	v_fma_f32 v5, v4, v5, 0.5
	v_ldexp_f32 v3, 1.0, v3
	v_mul_f32_e32 v5, v4, v5
	v_cndmask_b32_e32 v3, v3, v202, vcc
	v_fmac_f32_e32 v4, v4, v5
	v_add_f32_e32 v5, -1.0, v3
	v_fmac_f32_e32 v5, v3, v4
	v_add_f32_e32 v3, v5, v5
	v_cndmask_b32_e32 v3, v5, v3, vcc
	v_cmp_nlt_f32_e32 vcc, s22, v0
	v_exp_f32_e32 v2, v2
	s_nop 0
	v_cndmask_b32_e64 v3, v201, -v3, vcc
	v_cmp_gt_f32_e32 vcc, s23, v3
	v_mul_f32_e32 v4, 0x4f800000, v3
	s_nop 0
	v_cndmask_b32_e32 v3, v3, v4, vcc
	v_sqrt_f32_e32 v4, v3
	s_nop 0
	v_add_u32_e32 v5, -1, v4
	v_fma_f32 v6, -v5, v4, v3
	v_cmp_ge_f32_e64 s[0:1], 0, v6
	v_add_u32_e32 v6, 1, v4
	s_nop 0
	v_cndmask_b32_e64 v5, v4, v5, s[0:1]
	v_fma_f32 v4, -v6, v4, v3
	v_cmp_lt_f32_e64 s[0:1], 0, v4
	s_nop 1
	v_cndmask_b32_e64 v4, v5, v6, s[0:1]
	v_mul_f32_e32 v5, 0x37800000, v4
	v_cndmask_b32_e32 v4, v4, v5, vcc
	v_cmp_class_f32_e32 vcc, v3, v193
	s_nop 1
	v_cndmask_b32_e32 v3, v4, v3, vcc
	v_cmp_ngt_f32_e32 vcc, s24, v0
	s_nop 1
	v_cndmask_b32_e32 v0, 1.0, v3, vcc
	v_mul_f32_e32 v0, v1, v0
	v_mul_f32_e32 v0, v39, v0
	ds_write_b32 v144, v2 offset:2944
	ds_write_b32 v144, v0 offset:39808
	v_add_f32_e32 v0, v24, v36
	v_mul_f32_e32 v0, 0xbfb8aa3b, v0
	v_exp_f32_e32 v0, v0
	v_add_f32_e32 v1, v8, v38
	v_mul_f32_e32 v1, 0xbfb8aa3b, v1
	v_exp_f32_e32 v1, v1
	v_add_f32_e32 v0, 1.0, v0
	v_rcp_f32_e32 v0, v0
	v_add_f32_e32 v1, 1.0, v1
	v_rcp_f32_e32 v1, v1
	v_mul_f32_e32 v0, v0, v32
	v_mul_f32_e32 v2, 0x3fb8aa3b, v0
	v_add_f32_e32 v0, v0, v0
	v_mul_f32_e32 v3, 0x3fb8aa3b, v0
	v_rndne_f32_e32 v3, v3
	v_fmamk_f32 v4, v3, 0xbf317218, v0
	v_fmac_f32_e32 v4, 0x3102e308, v3
	v_fmamk_f32 v5, v4, 0x395133b1, v192
	v_cmp_eq_f32_e32 vcc, s21, v3
	v_cvt_i32_f32_e32 v3, v3
	v_fmaak_f32 v5, v4, v5, 0x3c0887f9
	v_fmaak_f32 v5, v4, v5, 0x3d2aaa81
	v_fmaak_f32 v5, v4, v5, 0x3e2aaaab
	v_fma_f32 v5, v4, v5, 0.5
	v_ldexp_f32 v3, 1.0, v3
	v_mul_f32_e32 v5, v4, v5
	v_cndmask_b32_e32 v3, v3, v202, vcc
	v_fmac_f32_e32 v4, v4, v5
	v_add_f32_e32 v5, -1.0, v3
	v_fmac_f32_e32 v5, v3, v4
	v_add_f32_e32 v3, v5, v5
	v_cndmask_b32_e32 v3, v5, v3, vcc
	v_cmp_nlt_f32_e32 vcc, s22, v0
	v_exp_f32_e32 v2, v2
	s_nop 0
	v_cndmask_b32_e64 v3, v201, -v3, vcc
	v_cmp_gt_f32_e32 vcc, s23, v3
	v_mul_f32_e32 v4, 0x4f800000, v3
	s_nop 0
	v_cndmask_b32_e32 v3, v3, v4, vcc
	v_sqrt_f32_e32 v4, v3
	s_nop 0
	v_add_u32_e32 v5, -1, v4
	v_fma_f32 v6, -v5, v4, v3
	v_cmp_ge_f32_e64 s[0:1], 0, v6
	v_add_u32_e32 v6, 1, v4
	s_nop 0
	v_cndmask_b32_e64 v5, v4, v5, s[0:1]
	v_fma_f32 v4, -v6, v4, v3
	v_cmp_lt_f32_e64 s[0:1], 0, v4
	s_nop 1
	v_cndmask_b32_e64 v4, v5, v6, s[0:1]
	v_mul_f32_e32 v5, 0x37800000, v4
	v_cndmask_b32_e32 v4, v4, v5, vcc
	v_cmp_class_f32_e32 vcc, v3, v193
	s_nop 1
	v_cndmask_b32_e32 v3, v4, v3, vcc
	v_cmp_ngt_f32_e32 vcc, s24, v0
	s_nop 1
	v_cndmask_b32_e32 v0, 1.0, v3, vcc
	v_mul_f32_e32 v0, v1, v0
	v_mul_f32_e32 v0, v55, v0
	ds_write_b32 v144, v2 offset:4224
	ds_write_b32 v144, v0 offset:41088
	v_add_f32_e32 v0, v25, v36
	v_mul_f32_e32 v0, 0xbfb8aa3b, v0
	v_exp_f32_e32 v0, v0
	v_add_f32_e32 v1, v9, v38
	v_mul_f32_e32 v1, 0xbfb8aa3b, v1
	v_exp_f32_e32 v1, v1
	v_add_f32_e32 v0, 1.0, v0
	v_rcp_f32_e32 v0, v0
	v_add_f32_e32 v1, 1.0, v1
	v_rcp_f32_e32 v1, v1
	v_mul_f32_e32 v0, v0, v32
	v_mul_f32_e32 v2, 0x3fb8aa3b, v0
	v_add_f32_e32 v0, v0, v0
	v_mul_f32_e32 v3, 0x3fb8aa3b, v0
	v_rndne_f32_e32 v3, v3
	v_fmamk_f32 v4, v3, 0xbf317218, v0
	v_fmac_f32_e32 v4, 0x3102e308, v3
	v_fmamk_f32 v5, v4, 0x395133b1, v192
	v_cmp_eq_f32_e32 vcc, s21, v3
	v_cvt_i32_f32_e32 v3, v3
	v_fmaak_f32 v5, v4, v5, 0x3c0887f9
	v_fmaak_f32 v5, v4, v5, 0x3d2aaa81
	v_fmaak_f32 v5, v4, v5, 0x3e2aaaab
	v_fma_f32 v5, v4, v5, 0.5
	v_ldexp_f32 v3, 1.0, v3
	v_mul_f32_e32 v5, v4, v5
	v_cndmask_b32_e32 v3, v3, v202, vcc
	v_fmac_f32_e32 v4, v4, v5
	v_add_f32_e32 v5, -1.0, v3
	v_fmac_f32_e32 v5, v3, v4
	v_add_f32_e32 v3, v5, v5
	v_cndmask_b32_e32 v3, v5, v3, vcc
	v_cmp_nlt_f32_e32 vcc, s22, v0
	v_exp_f32_e32 v2, v2
	s_nop 0
	v_cndmask_b32_e64 v3, v201, -v3, vcc
	v_cmp_gt_f32_e32 vcc, s23, v3
	v_mul_f32_e32 v4, 0x4f800000, v3
	s_nop 0
	v_cndmask_b32_e32 v3, v3, v4, vcc
	v_sqrt_f32_e32 v4, v3
	s_nop 0
	v_add_u32_e32 v5, -1, v4
	v_fma_f32 v6, -v5, v4, v3
	v_cmp_ge_f32_e64 s[0:1], 0, v6
	v_add_u32_e32 v6, 1, v4
	s_nop 0
	v_cndmask_b32_e64 v5, v4, v5, s[0:1]
	v_fma_f32 v4, -v6, v4, v3
	v_cmp_lt_f32_e64 s[0:1], 0, v4
	s_nop 1
	v_cndmask_b32_e64 v4, v5, v6, s[0:1]
	v_mul_f32_e32 v5, 0x37800000, v4
	v_cndmask_b32_e32 v4, v4, v5, vcc
	v_cmp_class_f32_e32 vcc, v3, v193
	s_nop 1
	v_cndmask_b32_e32 v3, v4, v3, vcc
	v_cmp_ngt_f32_e32 vcc, s24, v0
	s_nop 1
	v_cndmask_b32_e32 v0, 1.0, v3, vcc
	v_mul_f32_e32 v0, v1, v0
	v_mul_f32_e32 v0, v41, v0
	ds_write_b32 v144, v2 offset:4480
	ds_write_b32 v144, v0 offset:41344
	v_add_f32_e32 v0, v26, v36
	v_mul_f32_e32 v0, 0xbfb8aa3b, v0
	v_exp_f32_e32 v0, v0
	v_add_f32_e32 v1, v10, v38
	v_mul_f32_e32 v1, 0xbfb8aa3b, v1
	v_exp_f32_e32 v1, v1
	v_add_f32_e32 v0, 1.0, v0
	v_rcp_f32_e32 v0, v0
	v_add_f32_e32 v1, 1.0, v1
	v_rcp_f32_e32 v1, v1
	v_mul_f32_e32 v0, v0, v32
	v_mul_f32_e32 v2, 0x3fb8aa3b, v0
	v_add_f32_e32 v0, v0, v0
	v_mul_f32_e32 v3, 0x3fb8aa3b, v0
	v_rndne_f32_e32 v3, v3
	v_fmamk_f32 v4, v3, 0xbf317218, v0
	v_fmac_f32_e32 v4, 0x3102e308, v3
	v_fmamk_f32 v5, v4, 0x395133b1, v192
	v_cmp_eq_f32_e32 vcc, s21, v3
	v_cvt_i32_f32_e32 v3, v3
	v_fmaak_f32 v5, v4, v5, 0x3c0887f9
	v_fmaak_f32 v5, v4, v5, 0x3d2aaa81
	v_fmaak_f32 v5, v4, v5, 0x3e2aaaab
	v_fma_f32 v5, v4, v5, 0.5
	v_ldexp_f32 v3, 1.0, v3
	v_mul_f32_e32 v5, v4, v5
	v_cndmask_b32_e32 v3, v3, v202, vcc
	v_fmac_f32_e32 v4, v4, v5
	v_add_f32_e32 v5, -1.0, v3
	v_fmac_f32_e32 v5, v3, v4
	v_add_f32_e32 v3, v5, v5
	v_cndmask_b32_e32 v3, v5, v3, vcc
	v_cmp_nlt_f32_e32 vcc, s22, v0
	v_exp_f32_e32 v2, v2
	s_nop 0
	v_cndmask_b32_e64 v3, v201, -v3, vcc
	v_cmp_gt_f32_e32 vcc, s23, v3
	v_mul_f32_e32 v4, 0x4f800000, v3
	s_nop 0
	v_cndmask_b32_e32 v3, v3, v4, vcc
	v_sqrt_f32_e32 v4, v3
	s_nop 0
	v_add_u32_e32 v5, -1, v4
	v_fma_f32 v6, -v5, v4, v3
	v_cmp_ge_f32_e64 s[0:1], 0, v6
	v_add_u32_e32 v6, 1, v4
	s_nop 0
	v_cndmask_b32_e64 v5, v4, v5, s[0:1]
	v_fma_f32 v4, -v6, v4, v3
	v_cmp_lt_f32_e64 s[0:1], 0, v4
	s_nop 1
	v_cndmask_b32_e64 v4, v5, v6, s[0:1]
	v_mul_f32_e32 v5, 0x37800000, v4
	v_cndmask_b32_e32 v4, v4, v5, vcc
	v_cmp_class_f32_e32 vcc, v3, v193
	s_nop 1
	v_cndmask_b32_e32 v3, v4, v3, vcc
	v_cmp_ngt_f32_e32 vcc, s24, v0
	s_nop 1
	v_cndmask_b32_e32 v0, 1.0, v3, vcc
	v_mul_f32_e32 v0, v1, v0
	v_mul_f32_e32 v0, v57, v0
	ds_write_b32 v144, v2 offset:4736
	ds_write_b32 v144, v0 offset:41600
	v_add_f32_e32 v0, v27, v36
	v_mul_f32_e32 v0, 0xbfb8aa3b, v0
	v_exp_f32_e32 v0, v0
	v_add_f32_e32 v1, v11, v38
	v_mul_f32_e32 v1, 0xbfb8aa3b, v1
	v_exp_f32_e32 v1, v1
	v_add_f32_e32 v0, 1.0, v0
	v_rcp_f32_e32 v0, v0
	v_add_f32_e32 v1, 1.0, v1
	v_rcp_f32_e32 v1, v1
	v_mul_f32_e32 v0, v0, v32
	v_mul_f32_e32 v2, 0x3fb8aa3b, v0
	v_add_f32_e32 v0, v0, v0
	v_mul_f32_e32 v3, 0x3fb8aa3b, v0
	v_rndne_f32_e32 v3, v3
	v_fmamk_f32 v4, v3, 0xbf317218, v0
	v_fmac_f32_e32 v4, 0x3102e308, v3
	v_fmamk_f32 v5, v4, 0x395133b1, v192
	v_cmp_eq_f32_e32 vcc, s21, v3
	v_cvt_i32_f32_e32 v3, v3
	v_fmaak_f32 v5, v4, v5, 0x3c0887f9
	v_fmaak_f32 v5, v4, v5, 0x3d2aaa81
	v_fmaak_f32 v5, v4, v5, 0x3e2aaaab
	v_fma_f32 v5, v4, v5, 0.5
	v_ldexp_f32 v3, 1.0, v3
	v_mul_f32_e32 v5, v4, v5
	v_cndmask_b32_e32 v3, v3, v202, vcc
	v_fmac_f32_e32 v4, v4, v5
	v_add_f32_e32 v5, -1.0, v3
	v_fmac_f32_e32 v5, v3, v4
	v_add_f32_e32 v3, v5, v5
	v_cndmask_b32_e32 v3, v5, v3, vcc
	v_cmp_nlt_f32_e32 vcc, s22, v0
	v_exp_f32_e32 v2, v2
	s_nop 0
	v_cndmask_b32_e64 v3, v201, -v3, vcc
	v_cmp_gt_f32_e32 vcc, s23, v3
	v_mul_f32_e32 v4, 0x4f800000, v3
	s_nop 0
	v_cndmask_b32_e32 v3, v3, v4, vcc
	v_sqrt_f32_e32 v4, v3
	s_nop 0
	v_add_u32_e32 v5, -1, v4
	v_fma_f32 v6, -v5, v4, v3
	v_cmp_ge_f32_e64 s[0:1], 0, v6
	v_add_u32_e32 v6, 1, v4
	s_nop 0
	v_cndmask_b32_e64 v5, v4, v5, s[0:1]
	v_fma_f32 v4, -v6, v4, v3
	v_cmp_lt_f32_e64 s[0:1], 0, v4
	s_nop 1
	v_cndmask_b32_e64 v4, v5, v6, s[0:1]
	v_mul_f32_e32 v5, 0x37800000, v4
	v_cndmask_b32_e32 v4, v4, v5, vcc
	v_cmp_class_f32_e32 vcc, v3, v193
	s_nop 1
	v_cndmask_b32_e32 v3, v4, v3, vcc
	v_cmp_ngt_f32_e32 vcc, s24, v0
	s_nop 1
	v_cndmask_b32_e32 v0, 1.0, v3, vcc
	v_mul_f32_e32 v0, v1, v0
	v_mul_f32_e32 v0, v43, v0
	ds_write_b32 v144, v2 offset:4992
	ds_write_b32 v144, v0 offset:41856
	v_add_f32_e32 v0, v28, v36
	v_mul_f32_e32 v0, 0xbfb8aa3b, v0
	v_exp_f32_e32 v0, v0
	v_add_f32_e32 v1, v12, v38
	v_mul_f32_e32 v1, 0xbfb8aa3b, v1
	v_exp_f32_e32 v1, v1
	v_add_f32_e32 v0, 1.0, v0
	v_rcp_f32_e32 v0, v0
	v_add_f32_e32 v1, 1.0, v1
	v_rcp_f32_e32 v1, v1
	v_mul_f32_e32 v0, v0, v32
	v_mul_f32_e32 v2, 0x3fb8aa3b, v0
	v_add_f32_e32 v0, v0, v0
	v_mul_f32_e32 v3, 0x3fb8aa3b, v0
	v_rndne_f32_e32 v3, v3
	v_fmamk_f32 v4, v3, 0xbf317218, v0
	v_fmac_f32_e32 v4, 0x3102e308, v3
	v_fmamk_f32 v5, v4, 0x395133b1, v192
	v_cmp_eq_f32_e32 vcc, s21, v3
	v_cvt_i32_f32_e32 v3, v3
	v_fmaak_f32 v5, v4, v5, 0x3c0887f9
	v_fmaak_f32 v5, v4, v5, 0x3d2aaa81
	v_fmaak_f32 v5, v4, v5, 0x3e2aaaab
	v_fma_f32 v5, v4, v5, 0.5
	v_ldexp_f32 v3, 1.0, v3
	v_mul_f32_e32 v5, v4, v5
	v_cndmask_b32_e32 v3, v3, v202, vcc
	v_fmac_f32_e32 v4, v4, v5
	v_add_f32_e32 v5, -1.0, v3
	v_fmac_f32_e32 v5, v3, v4
	v_add_f32_e32 v3, v5, v5
	v_cndmask_b32_e32 v3, v5, v3, vcc
	v_cmp_nlt_f32_e32 vcc, s22, v0
	v_exp_f32_e32 v2, v2
	s_nop 0
	v_cndmask_b32_e64 v3, v201, -v3, vcc
	v_cmp_gt_f32_e32 vcc, s23, v3
	v_mul_f32_e32 v4, 0x4f800000, v3
	s_nop 0
	v_cndmask_b32_e32 v3, v3, v4, vcc
	v_sqrt_f32_e32 v4, v3
	s_nop 0
	v_add_u32_e32 v5, -1, v4
	v_fma_f32 v6, -v5, v4, v3
	v_cmp_ge_f32_e64 s[0:1], 0, v6
	v_add_u32_e32 v6, 1, v4
	s_nop 0
	v_cndmask_b32_e64 v5, v4, v5, s[0:1]
	v_fma_f32 v4, -v6, v4, v3
	v_cmp_lt_f32_e64 s[0:1], 0, v4
	s_nop 1
	v_cndmask_b32_e64 v4, v5, v6, s[0:1]
	v_mul_f32_e32 v5, 0x37800000, v4
	v_cndmask_b32_e32 v4, v4, v5, vcc
	v_cmp_class_f32_e32 vcc, v3, v193
	s_nop 1
	v_cndmask_b32_e32 v3, v4, v3, vcc
	v_cmp_ngt_f32_e32 vcc, s24, v0
	s_nop 1
	v_cndmask_b32_e32 v0, 1.0, v3, vcc
	v_mul_f32_e32 v0, v1, v0
	v_mul_f32_e32 v0, v59, v0
	ds_write_b32 v144, v2 offset:6272
	ds_write_b32 v144, v0 offset:43136
	v_add_f32_e32 v0, v29, v36
	v_mul_f32_e32 v0, 0xbfb8aa3b, v0
	v_exp_f32_e32 v0, v0
	v_add_f32_e32 v1, v13, v38
	v_mul_f32_e32 v1, 0xbfb8aa3b, v1
	v_exp_f32_e32 v1, v1
	v_add_f32_e32 v0, 1.0, v0
	v_rcp_f32_e32 v0, v0
	v_add_f32_e32 v1, 1.0, v1
	v_rcp_f32_e32 v1, v1
	v_mul_f32_e32 v0, v0, v32
	v_mul_f32_e32 v2, 0x3fb8aa3b, v0
	v_add_f32_e32 v0, v0, v0
	v_mul_f32_e32 v3, 0x3fb8aa3b, v0
	v_rndne_f32_e32 v3, v3
	v_fmamk_f32 v4, v3, 0xbf317218, v0
	v_fmac_f32_e32 v4, 0x3102e308, v3
	v_fmamk_f32 v5, v4, 0x395133b1, v192
	v_cmp_eq_f32_e32 vcc, s21, v3
	v_cvt_i32_f32_e32 v3, v3
	v_fmaak_f32 v5, v4, v5, 0x3c0887f9
	v_fmaak_f32 v5, v4, v5, 0x3d2aaa81
	v_fmaak_f32 v5, v4, v5, 0x3e2aaaab
	v_fma_f32 v5, v4, v5, 0.5
	v_ldexp_f32 v3, 1.0, v3
	v_mul_f32_e32 v5, v4, v5
	v_cndmask_b32_e32 v3, v3, v202, vcc
	v_fmac_f32_e32 v4, v4, v5
	v_add_f32_e32 v5, -1.0, v3
	v_fmac_f32_e32 v5, v3, v4
	v_add_f32_e32 v3, v5, v5
	v_cndmask_b32_e32 v3, v5, v3, vcc
	v_cmp_nlt_f32_e32 vcc, s22, v0
	v_exp_f32_e32 v2, v2
	s_nop 0
	v_cndmask_b32_e64 v3, v201, -v3, vcc
	v_cmp_gt_f32_e32 vcc, s23, v3
	v_mul_f32_e32 v4, 0x4f800000, v3
	s_nop 0
	v_cndmask_b32_e32 v3, v3, v4, vcc
	v_sqrt_f32_e32 v4, v3
	s_nop 0
	v_add_u32_e32 v5, -1, v4
	v_fma_f32 v6, -v5, v4, v3
	v_cmp_ge_f32_e64 s[0:1], 0, v6
	v_add_u32_e32 v6, 1, v4
	s_nop 0
	v_cndmask_b32_e64 v5, v4, v5, s[0:1]
	v_fma_f32 v4, -v6, v4, v3
	v_cmp_lt_f32_e64 s[0:1], 0, v4
	s_nop 1
	v_cndmask_b32_e64 v4, v5, v6, s[0:1]
	v_mul_f32_e32 v5, 0x37800000, v4
	v_cndmask_b32_e32 v4, v4, v5, vcc
	v_cmp_class_f32_e32 vcc, v3, v193
	s_nop 1
	v_cndmask_b32_e32 v3, v4, v3, vcc
	v_cmp_ngt_f32_e32 vcc, s24, v0
	s_nop 1
	v_cndmask_b32_e32 v0, 1.0, v3, vcc
	v_mul_f32_e32 v0, v1, v0
	v_mul_f32_e32 v0, v45, v0
	ds_write_b32 v144, v2 offset:6528
	ds_write_b32 v144, v0 offset:43392
	v_add_f32_e32 v0, v30, v36
	v_mul_f32_e32 v0, 0xbfb8aa3b, v0
	v_exp_f32_e32 v0, v0
	v_add_f32_e32 v1, v14, v38
	v_mul_f32_e32 v1, 0xbfb8aa3b, v1
	v_exp_f32_e32 v1, v1
	v_add_f32_e32 v0, 1.0, v0
	v_rcp_f32_e32 v0, v0
	v_add_f32_e32 v1, 1.0, v1
	v_rcp_f32_e32 v1, v1
	v_mul_f32_e32 v0, v0, v32
	v_mul_f32_e32 v2, 0x3fb8aa3b, v0
	v_add_f32_e32 v0, v0, v0
	v_mul_f32_e32 v3, 0x3fb8aa3b, v0
	v_rndne_f32_e32 v3, v3
	v_fmamk_f32 v4, v3, 0xbf317218, v0
	v_fmac_f32_e32 v4, 0x3102e308, v3
	v_fmamk_f32 v5, v4, 0x395133b1, v192
	v_cmp_eq_f32_e32 vcc, s21, v3
	v_cvt_i32_f32_e32 v3, v3
	v_fmaak_f32 v5, v4, v5, 0x3c0887f9
	v_fmaak_f32 v5, v4, v5, 0x3d2aaa81
	v_fmaak_f32 v5, v4, v5, 0x3e2aaaab
	v_fma_f32 v5, v4, v5, 0.5
	v_ldexp_f32 v3, 1.0, v3
	v_mul_f32_e32 v5, v4, v5
	v_cndmask_b32_e32 v3, v3, v202, vcc
	v_fmac_f32_e32 v4, v4, v5
	v_add_f32_e32 v5, -1.0, v3
	v_fmac_f32_e32 v5, v3, v4
	v_add_f32_e32 v3, v5, v5
	v_cndmask_b32_e32 v3, v5, v3, vcc
	v_cmp_nlt_f32_e32 vcc, s22, v0
	v_exp_f32_e32 v2, v2
	s_nop 0
	v_cndmask_b32_e64 v3, v201, -v3, vcc
	v_cmp_gt_f32_e32 vcc, s23, v3
	v_mul_f32_e32 v4, 0x4f800000, v3
	s_nop 0
	v_cndmask_b32_e32 v3, v3, v4, vcc
	v_sqrt_f32_e32 v4, v3
	s_nop 0
	v_add_u32_e32 v5, -1, v4
	v_fma_f32 v6, -v5, v4, v3
	v_cmp_ge_f32_e64 s[0:1], 0, v6
	v_add_u32_e32 v6, 1, v4
	s_nop 0
	v_cndmask_b32_e64 v5, v4, v5, s[0:1]
	v_fma_f32 v4, -v6, v4, v3
	v_cmp_lt_f32_e64 s[0:1], 0, v4
	s_nop 1
	v_cndmask_b32_e64 v4, v5, v6, s[0:1]
	v_mul_f32_e32 v5, 0x37800000, v4
	v_cndmask_b32_e32 v4, v4, v5, vcc
	v_cmp_class_f32_e32 vcc, v3, v193
	s_nop 1
	v_cndmask_b32_e32 v3, v4, v3, vcc
	v_cmp_ngt_f32_e32 vcc, s24, v0
	s_nop 1
	v_cndmask_b32_e32 v0, 1.0, v3, vcc
	v_mul_f32_e32 v0, v1, v0
	v_mul_f32_e32 v0, v35, v0
	v_add_u32_e32 v1, 0x1800, v144
	ds_write2_b32 v1, v2, v34 offset0:160 offset1:192
	ds_write_b32 v144, v0 offset:43648
	v_add_f32_e32 v0, v31, v36
	v_mul_f32_e32 v0, 0xbfb8aa3b, v0
	v_exp_f32_e32 v0, v0
	v_add_f32_e32 v1, v15, v38
	v_mul_f32_e32 v1, 0xbfb8aa3b, v1
	v_exp_f32_e32 v1, v1
	v_add_f32_e32 v0, 1.0, v0
	v_rcp_f32_e32 v0, v0
	v_add_f32_e32 v1, 1.0, v1
	v_rcp_f32_e32 v1, v1
	v_mul_f32_e32 v0, v0, v32
	v_mul_f32_e32 v2, 0x3fb8aa3b, v0
	v_add_f32_e32 v0, v0, v0
	v_mul_f32_e32 v3, 0x3fb8aa3b, v0
	v_rndne_f32_e32 v3, v3
	v_fmamk_f32 v4, v3, 0xbf317218, v0
	v_fmac_f32_e32 v4, 0x3102e308, v3
	v_fmamk_f32 v5, v4, 0x395133b1, v192
	v_cmp_eq_f32_e32 vcc, s21, v3
	v_cvt_i32_f32_e32 v3, v3
	v_fmaak_f32 v5, v4, v5, 0x3c0887f9
	v_fmaak_f32 v5, v4, v5, 0x3d2aaa81
	v_fmaak_f32 v5, v4, v5, 0x3e2aaaab
	v_fma_f32 v5, v4, v5, 0.5
	v_ldexp_f32 v3, 1.0, v3
	v_mul_f32_e32 v5, v4, v5
	v_cndmask_b32_e32 v3, v3, v202, vcc
	v_fmac_f32_e32 v4, v4, v5
	v_add_f32_e32 v5, -1.0, v3
	v_fmac_f32_e32 v5, v3, v4
	v_add_f32_e32 v3, v5, v5
	v_cndmask_b32_e32 v3, v5, v3, vcc
	v_cmp_nlt_f32_e32 vcc, s22, v0
	v_exp_f32_e32 v2, v2
	s_mov_b32 s21, 0x84000
	v_cndmask_b32_e64 v3, v201, -v3, vcc
	v_cmp_gt_f32_e32 vcc, s23, v3
	v_mul_f32_e32 v4, 0x4f800000, v3
	s_mov_b32 s22, 0x2d000
	v_cndmask_b32_e32 v3, v3, v4, vcc
	v_sqrt_f32_e32 v4, v3
	s_mov_b32 s23, 0x59000
	v_add_u32_e32 v5, -1, v4
	v_fma_f32 v6, -v5, v4, v3
	v_cmp_ge_f32_e64 s[0:1], 0, v6
	v_add_u32_e32 v6, 1, v4
	s_nop 0
	v_cndmask_b32_e64 v5, v4, v5, s[0:1]
	v_fma_f32 v4, -v6, v4, v3
	v_cmp_lt_f32_e64 s[0:1], 0, v4
	s_nop 1
	v_cndmask_b32_e64 v4, v5, v6, s[0:1]
	v_mul_f32_e32 v5, 0x37800000, v4
	v_cndmask_b32_e32 v4, v4, v5, vcc
	v_cmp_class_f32_e32 vcc, v3, v193
	v_mov_b32_e32 v5, 0
	s_nop 0
	v_cndmask_b32_e32 v3, v4, v3, vcc
	v_cmp_ngt_f32_e32 vcc, s24, v0
	v_readlane_b32 s24, v248, 7
	s_nop 0
	v_cndmask_b32_e32 v0, 1.0, v3, vcc
	v_mul_f32_e32 v0, v1, v0
	v_mul_f32_e32 v0, v33, v0
	ds_write_b32 v144, v2 offset:7040
	ds_write_b32 v144, v0 offset:43904
	v_mov_b32_e32 v0, 0
	s_waitcnt lgkmcnt(0)
	s_barrier
	s_cbranch_scc1 .LBB0_915
	v_lshl_add_u64 v[2:3], v[64:65], 0, s[4:5]
	v_add_co_u32_e32 v4, vcc, 0x13000, v2
	s_sub_i32 s0, s2, s12
	s_nop 0
	v_addc_co_u32_e32 v5, vcc, 0, v3, vcc
	global_load_dwordx2 v[4:5], v[4:5], off
	s_cmp_eq_u32 s0, 1
	s_waitcnt vmcnt(0)
	v_fmac_f32_e32 v5, 0, v4
	s_cbranch_scc1 .LBB0_915
	v_add_co_u32_e32 v2, vcc, 0x12000, v2
	s_cmp_eq_u32 s0, 2
	s_nop 0
	v_addc_co_u32_e32 v3, vcc, 0, v3, vcc
	global_load_dwordx2 v[2:3], v[2:3], off
	s_waitcnt vmcnt(0)
	v_fmac_f32_e32 v3, v5, v2
	s_cbranch_scc1 .LBB0_914
	s_mul_i32 s1, s11, 36
	s_add_i32 s2, s1, 36
	s_ashr_i32 s3, s2, 31
	s_lshl_b64 s[2:3], s[2:3], 12
	v_readlane_b32 s1, v249, 47
	s_add_u32 s2, s1, s2
	v_readlane_b32 s1, v249, 48
	v_add_lshl_u32 v96, s13, v141, 3
	s_addc_u32 s3, s1, s3
	v_lshl_add_u64 v[4:5], s[2:3], 0, v[96:97]
	s_add_i32 s0, s0, -2

.LBB0_947:
	s_or_b64 exec, exec, s[0:1]
	v_add_f32_e32 v0, 0, v110
	v_add_f32_e32 v0, v0, v111
	v_add_f32_e32 v0, v0, v109
	v_cvt_pk_bf16_f32 v110, v110, v111
	v_cvt_pk_bf16_f32 v111, v109, v112
	v_xor_b32_e32 v109, 16, v105
	v_cmp_lt_i32_e64 s[0:1], v109, v106
	v_add_f32_e32 v118, v0, v112
	v_lshl_add_u32 v113, v99, 3, 0
	v_cndmask_b32_e64 v109, v105, v109, s[0:1]
	v_lshlrev_b32_e32 v229, 2, v109
	v_mul_lo_u32 v0, v100, s87
	v_mov_b32_e32 v109, v118
	v_mov_b32_e32 v255, v118
	s_nop 1
	v_permlane16_swap_b32_e32 v109, v255
	v_add_u32_e32 v0, v113, v0
	ds_write_b64 v0, v[110:111] offset:34816
	v_xor_b32_e32 v110, 8, v105
	v_cmp_lt_i32_e64 s[0:1], v110, v106
	s_waitcnt lgkmcnt(1)
	v_add_f32_e32 v109, v109, v255
	v_cmp_eq_u32_e32 vcc, 0, v99
	v_cndmask_b32_e64 v110, v105, v110, s[0:1]
	v_lshlrev_b32_e32 v230, 2, v110
	s_waitcnt lgkmcnt(0)
	v_add_f32_dpp v109, v109, v109 row_ror:8 row_mask:0xf bank_mask:0xf
	v_xor_b32_e32 v110, 4, v105
	v_cmp_lt_i32_e64 s[0:1], v110, v106
	s_nop 1
	v_cndmask_b32_e64 v110, v105, v110, s[0:1]
	v_lshlrev_b32_e32 v231, 2, v110
	v_mov_b32_dpp v110, v109 row_shl:4 row_mask:0xf bank_mask:0x5
	v_mov_b32_dpp v110, v109 row_shr:4 row_mask:0xf bank_mask:0xa
	v_add_f32_e32 v109, v109, v110
	v_xor_b32_e32 v110, 2, v105
	v_cmp_lt_i32_e64 s[0:1], v110, v106
	s_nop 1
	v_cndmask_b32_e64 v110, v105, v110, s[0:1]
	v_lshlrev_b32_e32 v232, 2, v110
	v_add_f32_dpp v109, v109, v109 quad_perm:[2,3,0,1] row_mask:0xf bank_mask:0xf
	v_xor_b32_e32 v110, 1, v105
	v_cmp_lt_i32_e64 s[0:1], v110, v106
	s_nop 1
	v_cndmask_b32_e64 v105, v105, v110, s[0:1]
	v_lshlrev_b32_e32 v233, 2, v105
	v_mov_b32_dpp v105, v109 quad_perm:[1,0,3,2] row_mask:0xf bank_mask:0xf
	s_and_saveexec_b64 s[0:1], vcc
	s_cbranch_execz .LBB0_949
	s_waitcnt lgkmcnt(0)
	v_add_f32_e32 v105, v109, v105
	s_waitcnt vmcnt(0)
	v_sub_f32_e32 v106, v96, v108
	v_add_u32_e32 v109, 0x11c00, v107
	v_mul_f32_e32 v106, 0x3fb8aa3b, v106
	ds_read_b32 v109, v109
	v_exp_f32_e32 v106, v106
	s_waitcnt lgkmcnt(0)
	v_fmac_f32_e32 v105, v106, v109
	v_add_u32_e32 v109, 0x11e00, v107
	ds_write_b32 v109, v105
	v_add_u32_e32 v105, 0x12000, v107
	ds_write_b32 v105, v106
	v_add_u32_e32 v105, 0x11800, v107
	ds_read_b32 v105, v105
	v_add_u32_e32 v106, 0x12200, v107
	s_waitcnt lgkmcnt(0)
	v_add_f32_e32 v105, v108, v105
	v_mul_f32_e32 v105, 0xbfb8aa3b, v105
	v_exp_f32_e32 v105, v105
	ds_write_b32 v106, v105

.LBB0_987:
	s_or_b64 exec, exec, s[68:69]
	v_add_f32_e32 v4, 0, v17
	v_add_f32_e32 v4, v4, v3
	v_add_f32_e32 v4, v4, v19
	v_add_f32_e32 v4, v4, v18
	v_cvt_pk_bf16_f32 v34, v17, v3
	v_mov_b32_e32 v3, v4
	v_mov_b32_e32 v255, v4
	s_nop 1
	v_permlane16_swap_b32_e32 v3, v255
	v_cvt_pk_bf16_f32 v35, v19, v18
	ds_write_b64 v0, v[34:35] offset:36992
	s_waitcnt lgkmcnt(1)
	v_add_f32_e32 v3, v3, v255
	s_nop 1
	v_mov_b32_dpp v4, v3 row_ror:8 row_mask:0xf bank_mask:0xf
	s_waitcnt lgkmcnt(0)
	v_add_f32_e32 v3, v3, v4
	s_nop 1
	v_mov_b32_dpp v4, v3 row_shl:4 row_mask:0xf bank_mask:0x5
	v_mov_b32_dpp v4, v3 row_shr:4 row_mask:0xf bank_mask:0xa
	s_nop 0
	v_add_f32_e32 v3, v3, v4
	s_nop 1
	v_mov_b32_dpp v4, v3 quad_perm:[2,3,0,1] row_mask:0xf bank_mask:0xf
	s_nop 0
	v_add_f32_e32 v3, v3, v4
	s_nop 1
	v_mov_b32_dpp v4, v3 quad_perm:[1,0,3,2] row_mask:0xf bank_mask:0xf
	s_and_saveexec_b64 s[0:1], vcc
	s_cbranch_execz .LBB0_989
	v_lshl_add_u32 v2, v2, 2, 0
	s_waitcnt lgkmcnt(0)
	v_add_f32_e32 v3, v3, v4
	s_waitcnt vmcnt(0)
	v_sub_f32_e32 v4, v96, v1
	v_add_u32_e32 v17, 0x11c00, v2
	v_mul_f32_e32 v4, 0x3fb8aa3b, v4
	ds_read_b32 v17, v17
	v_exp_f32_e32 v4, v4
	s_waitcnt lgkmcnt(0)
	v_fmac_f32_e32 v3, v4, v17
	v_add_u32_e32 v17, 0x11e00, v2
	ds_write_b32 v17, v3
	v_add_u32_e32 v3, 0x12000, v2
	ds_write_b32 v3, v4
	v_add_u32_e32 v3, 0x11800, v2
	ds_read_b32 v3, v3
	v_add_u32_e32 v2, 0x12200, v2
	s_waitcnt lgkmcnt(0)
	v_add_f32_e32 v1, v1, v3
	v_mul_f32_e32 v1, 0xbfb8aa3b, v1
	v_exp_f32_e32 v1, v1
	ds_write_b32 v2, v1

.LBB0_997:
	s_or_b64 exec, exec, s[68:69]
	v_add_f32_e32 v5, 0, v4
	v_add_f32_e32 v5, v5, v3
	v_add_f32_e32 v5, v5, v18
	v_add_f32_e32 v19, v5, v17
	v_cvt_pk_bf16_f32 v4, v4, v3
	v_mov_b32_e32 v3, v19
	v_mov_b32_e32 v255, v19
	s_nop 1
	v_permlane16_swap_b32_e32 v3, v255
	v_cvt_pk_bf16_f32 v5, v18, v17
	ds_write_b64 v0, v[4:5] offset:37264
	s_waitcnt lgkmcnt(1)
	v_add_f32_e32 v3, v3, v255
	s_nop 1
	v_mov_b32_dpp v4, v3 row_ror:8 row_mask:0xf bank_mask:0xf
	s_waitcnt lgkmcnt(0)
	v_add_f32_e32 v3, v3, v4
	s_nop 1
	v_mov_b32_dpp v4, v3 row_shl:4 row_mask:0xf bank_mask:0x5
	v_mov_b32_dpp v4, v3 row_shr:4 row_mask:0xf bank_mask:0xa
	s_nop 0
	v_add_f32_e32 v3, v3, v4
	s_nop 1
	v_mov_b32_dpp v4, v3 quad_perm:[2,3,0,1] row_mask:0xf bank_mask:0xf
	s_nop 0
	v_add_f32_e32 v3, v3, v4
	s_nop 1
	v_mov_b32_dpp v4, v3 quad_perm:[1,0,3,2] row_mask:0xf bank_mask:0xf
	s_and_saveexec_b64 s[0:1], vcc
	s_cbranch_execz .LBB0_999
	v_lshl_add_u32 v2, v2, 2, 0
	s_waitcnt lgkmcnt(0)
	v_add_f32_e32 v3, v3, v4
	s_waitcnt vmcnt(0)
	v_sub_f32_e32 v4, v96, v1
	v_add_u32_e32 v5, 0x11c00, v2
	v_mul_f32_e32 v4, 0x3fb8aa3b, v4
	ds_read_b32 v5, v5
	v_exp_f32_e32 v4, v4
	s_waitcnt lgkmcnt(0)
	v_fmac_f32_e32 v3, v4, v5
	v_add_u32_e32 v5, 0x11e00, v2
	ds_write_b32 v5, v3
	v_add_u32_e32 v3, 0x12000, v2
	ds_write_b32 v3, v4
	v_add_u32_e32 v3, 0x11800, v2
	ds_read_b32 v3, v3
	v_add_u32_e32 v2, 0x12200, v2
	s_waitcnt lgkmcnt(0)
	v_add_f32_e32 v1, v1, v3
	v_mul_f32_e32 v1, 0xbfb8aa3b, v1
	v_exp_f32_e32 v1, v1
	ds_write_b32 v2, v1

.LBB0_1007:
	s_or_b64 exec, exec, s[68:69]
	v_add_f32_e32 v6, 0, v4
	v_add_f32_e32 v6, v6, v3
	v_add_f32_e32 v6, v6, v17
	v_add_f32_e32 v6, v6, v5
	v_cvt_pk_bf16_f32 v4, v4, v3
	v_mov_b32_e32 v3, v6
	v_mov_b32_e32 v255, v6
	s_nop 1
	v_permlane16_swap_b32_e32 v3, v255
	v_cvt_pk_bf16_f32 v5, v17, v5
	ds_write_b64 v0, v[4:5] offset:37536
	s_waitcnt lgkmcnt(1)
	v_add_f32_e32 v3, v3, v255
	s_nop 1
	v_mov_b32_dpp v4, v3 row_ror:8 row_mask:0xf bank_mask:0xf
	s_waitcnt lgkmcnt(0)
	v_add_f32_e32 v3, v3, v4
	s_nop 1
	v_mov_b32_dpp v4, v3 row_shl:4 row_mask:0xf bank_mask:0x5
	v_mov_b32_dpp v4, v3 row_shr:4 row_mask:0xf bank_mask:0xa
	s_nop 0
	v_add_f32_e32 v3, v3, v4
	s_nop 1
	v_mov_b32_dpp v4, v3 quad_perm:[2,3,0,1] row_mask:0xf bank_mask:0xf
	s_nop 0
	v_add_f32_e32 v3, v3, v4
	s_nop 1
	v_mov_b32_dpp v4, v3 quad_perm:[1,0,3,2] row_mask:0xf bank_mask:0xf
	s_and_saveexec_b64 s[0:1], vcc
	s_cbranch_execz .LBB0_1009
	v_lshl_add_u32 v2, v2, 2, 0
	s_waitcnt lgkmcnt(0)
	v_add_f32_e32 v3, v3, v4
	s_waitcnt vmcnt(0)
	v_sub_f32_e32 v4, v96, v1
	v_add_u32_e32 v5, 0x11c00, v2
	v_mul_f32_e32 v4, 0x3fb8aa3b, v4
	ds_read_b32 v5, v5
	v_exp_f32_e32 v4, v4
	s_waitcnt lgkmcnt(0)
	v_fmac_f32_e32 v3, v4, v5
	v_add_u32_e32 v5, 0x11e00, v2
	ds_write_b32 v5, v3
	v_add_u32_e32 v3, 0x12000, v2
	ds_write_b32 v3, v4
	v_add_u32_e32 v3, 0x11800, v2
	ds_read_b32 v3, v3
	v_add_u32_e32 v2, 0x12200, v2
	s_waitcnt lgkmcnt(0)
	v_add_f32_e32 v1, v1, v3
	v_mul_f32_e32 v1, 0xbfb8aa3b, v1
	v_exp_f32_e32 v1, v1
	ds_write_b32 v2, v1

.LBB0_1017:
	s_or_b64 exec, exec, s[68:69]
	v_add_f32_e32 v7, 0, v4
	v_add_f32_e32 v7, v7, v3
	v_add_f32_e32 v7, v7, v6
	v_add_f32_e32 v7, v7, v5
	v_cvt_pk_bf16_f32 v4, v4, v3
	v_mov_b32_e32 v3, v7
	v_mov_b32_e32 v255, v7
	s_nop 1
	v_permlane16_swap_b32_e32 v3, v255
	v_cvt_pk_bf16_f32 v5, v6, v5
	ds_write_b64 v0, v[4:5] offset:37808
	s_waitcnt lgkmcnt(1)
	v_add_f32_e32 v3, v3, v255
	s_nop 1
	v_mov_b32_dpp v4, v3 row_ror:8 row_mask:0xf bank_mask:0xf
	s_waitcnt lgkmcnt(0)
	v_add_f32_e32 v3, v3, v4
	s_nop 1
	v_mov_b32_dpp v4, v3 row_shl:4 row_mask:0xf bank_mask:0x5
	v_mov_b32_dpp v4, v3 row_shr:4 row_mask:0xf bank_mask:0xa
	s_nop 0
	v_add_f32_e32 v3, v3, v4
	s_nop 1
	v_mov_b32_dpp v4, v3 quad_perm:[2,3,0,1] row_mask:0xf bank_mask:0xf
	s_nop 0
	v_add_f32_e32 v3, v3, v4
	s_nop 1
	v_mov_b32_dpp v4, v3 quad_perm:[1,0,3,2] row_mask:0xf bank_mask:0xf
	s_and_saveexec_b64 s[0:1], vcc
	s_cbranch_execz .LBB0_1019
	v_lshl_add_u32 v2, v2, 2, 0
	s_waitcnt lgkmcnt(0)
	v_add_f32_e32 v3, v3, v4
	s_waitcnt vmcnt(0)
	v_sub_f32_e32 v4, v96, v1
	v_add_u32_e32 v5, 0x11c00, v2
	v_mul_f32_e32 v4, 0x3fb8aa3b, v4
	ds_read_b32 v5, v5
	v_exp_f32_e32 v4, v4
	s_waitcnt lgkmcnt(0)
	v_fmac_f32_e32 v3, v4, v5
	v_add_u32_e32 v5, 0x11e00, v2
	ds_write_b32 v5, v3
	v_add_u32_e32 v3, 0x12000, v2
	ds_write_b32 v3, v4
	v_add_u32_e32 v3, 0x11800, v2
	ds_read_b32 v3, v3
	v_add_u32_e32 v2, 0x12200, v2
	s_waitcnt lgkmcnt(0)
	v_add_f32_e32 v1, v1, v3
	v_mul_f32_e32 v1, 0xbfb8aa3b, v1
	v_exp_f32_e32 v1, v1
	ds_write_b32 v2, v1

.LBB0_1027:
	s_or_b64 exec, exec, s[68:69]
	v_add_f32_e32 v7, 0, v4
	v_add_f32_e32 v7, v7, v3
	v_add_f32_e32 v7, v7, v6
	v_add_f32_e32 v7, v7, v5
	v_cvt_pk_bf16_f32 v4, v4, v3
	v_mov_b32_e32 v3, v7
	v_mov_b32_e32 v255, v7
	s_nop 1
	v_permlane16_swap_b32_e32 v3, v255
	v_cvt_pk_bf16_f32 v5, v6, v5
	ds_write_b64 v0, v[4:5] offset:39168
	s_waitcnt lgkmcnt(1)
	v_add_f32_e32 v3, v3, v255
	s_nop 1
	v_mov_b32_dpp v4, v3 row_ror:8 row_mask:0xf bank_mask:0xf
	s_waitcnt lgkmcnt(0)
	v_add_f32_e32 v3, v3, v4
	s_nop 1
	v_mov_b32_dpp v4, v3 row_shl:4 row_mask:0xf bank_mask:0x5
	v_mov_b32_dpp v4, v3 row_shr:4 row_mask:0xf bank_mask:0xa
	s_nop 0
	v_add_f32_e32 v3, v3, v4
	s_nop 1
	v_mov_b32_dpp v4, v3 quad_perm:[2,3,0,1] row_mask:0xf bank_mask:0xf
	s_nop 0
	v_add_f32_e32 v3, v3, v4
	s_nop 1
	v_mov_b32_dpp v4, v3 quad_perm:[1,0,3,2] row_mask:0xf bank_mask:0xf
	s_and_saveexec_b64 s[0:1], vcc
	s_cbranch_execz .LBB0_1029
	v_lshl_add_u32 v2, v2, 2, 0
	s_waitcnt lgkmcnt(0)
	v_add_f32_e32 v3, v3, v4
	s_waitcnt vmcnt(0)
	v_sub_f32_e32 v4, v96, v1
	v_add_u32_e32 v5, 0x11c00, v2
	v_mul_f32_e32 v4, 0x3fb8aa3b, v4
	ds_read_b32 v5, v5
	v_exp_f32_e32 v4, v4
	s_waitcnt lgkmcnt(0)
	v_fmac_f32_e32 v3, v4, v5
	v_add_u32_e32 v5, 0x11e00, v2
	ds_write_b32 v5, v3
	v_add_u32_e32 v3, 0x12000, v2
	ds_write_b32 v3, v4
	v_add_u32_e32 v3, 0x11800, v2
	ds_read_b32 v3, v3
	v_add_u32_e32 v2, 0x12200, v2
	s_waitcnt lgkmcnt(0)
	v_add_f32_e32 v1, v1, v3
	v_mul_f32_e32 v1, 0xbfb8aa3b, v1
	v_exp_f32_e32 v1, v1
	ds_write_b32 v2, v1

.LBB0_1037:
	s_or_b64 exec, exec, s[68:69]
	v_add_f32_e32 v7, 0, v4
	v_add_f32_e32 v7, v7, v3
	v_add_f32_e32 v7, v7, v6
	v_add_f32_e32 v7, v7, v5
	v_cvt_pk_bf16_f32 v4, v4, v3
	v_mov_b32_e32 v3, v7
	v_mov_b32_e32 v255, v7
	s_nop 1
	v_permlane16_swap_b32_e32 v3, v255
	v_cvt_pk_bf16_f32 v5, v6, v5
	ds_write_b64 v0, v[4:5] offset:39440
	s_waitcnt lgkmcnt(1)
	v_add_f32_e32 v3, v3, v255
	s_nop 1
	v_mov_b32_dpp v4, v3 row_ror:8 row_mask:0xf bank_mask:0xf
	s_waitcnt lgkmcnt(0)
	v_add_f32_e32 v3, v3, v4
	s_nop 1
	v_mov_b32_dpp v4, v3 row_shl:4 row_mask:0xf bank_mask:0x5
	v_mov_b32_dpp v4, v3 row_shr:4 row_mask:0xf bank_mask:0xa
	s_nop 0
	v_add_f32_e32 v3, v3, v4
	s_nop 1
	v_mov_b32_dpp v4, v3 quad_perm:[2,3,0,1] row_mask:0xf bank_mask:0xf
	s_nop 0
	v_add_f32_e32 v3, v3, v4
	s_nop 1
	v_mov_b32_dpp v4, v3 quad_perm:[1,0,3,2] row_mask:0xf bank_mask:0xf
	s_and_saveexec_b64 s[0:1], vcc
	s_cbranch_execz .LBB0_1039
	v_lshl_add_u32 v2, v2, 2, 0
	s_waitcnt lgkmcnt(0)
	v_add_f32_e32 v3, v3, v4
	s_waitcnt vmcnt(0)
	v_sub_f32_e32 v4, v96, v1
	v_add_u32_e32 v5, 0x11c00, v2
	v_mul_f32_e32 v4, 0x3fb8aa3b, v4
	ds_read_b32 v5, v5
	v_exp_f32_e32 v4, v4
	s_waitcnt lgkmcnt(0)
	v_fmac_f32_e32 v3, v4, v5
	v_add_u32_e32 v5, 0x11e00, v2
	ds_write_b32 v5, v3
	v_add_u32_e32 v3, 0x12000, v2
	ds_write_b32 v3, v4
	v_add_u32_e32 v3, 0x11800, v2
	ds_read_b32 v3, v3
	v_add_u32_e32 v2, 0x12200, v2
	s_waitcnt lgkmcnt(0)
	v_add_f32_e32 v1, v1, v3
	v_mul_f32_e32 v1, 0xbfb8aa3b, v1
	v_exp_f32_e32 v1, v1
	ds_write_b32 v2, v1

.LBB0_1047:
	s_or_b64 exec, exec, s[68:69]
	v_add_f32_e32 v7, 0, v4
	v_add_f32_e32 v7, v7, v3
	v_add_f32_e32 v7, v7, v6
	v_add_f32_e32 v7, v7, v5
	v_cvt_pk_bf16_f32 v4, v4, v3
	v_mov_b32_e32 v3, v7
	v_mov_b32_e32 v255, v7
	s_nop 1
	v_permlane16_swap_b32_e32 v3, v255
	v_cvt_pk_bf16_f32 v5, v6, v5
	ds_write_b64 v0, v[4:5] offset:39712
	s_waitcnt lgkmcnt(1)
	v_add_f32_e32 v3, v3, v255
	s_nop 1
	v_mov_b32_dpp v4, v3 row_ror:8 row_mask:0xf bank_mask:0xf
	s_waitcnt lgkmcnt(0)
	v_add_f32_e32 v3, v3, v4
	s_nop 1
	v_mov_b32_dpp v4, v3 row_shl:4 row_mask:0xf bank_mask:0x5
	v_mov_b32_dpp v4, v3 row_shr:4 row_mask:0xf bank_mask:0xa
	s_nop 0
	v_add_f32_e32 v3, v3, v4
	s_nop 1
	v_mov_b32_dpp v4, v3 quad_perm:[2,3,0,1] row_mask:0xf bank_mask:0xf
	s_nop 0
	v_add_f32_e32 v3, v3, v4
	s_nop 1
	v_mov_b32_dpp v4, v3 quad_perm:[1,0,3,2] row_mask:0xf bank_mask:0xf
	s_and_saveexec_b64 s[0:1], vcc
	s_cbranch_execz .LBB0_1049
	v_lshl_add_u32 v2, v2, 2, 0
	s_waitcnt lgkmcnt(0)
	v_add_f32_e32 v3, v3, v4
	s_waitcnt vmcnt(0)
	v_sub_f32_e32 v4, v96, v1
	v_add_u32_e32 v5, 0x11c00, v2
	v_mul_f32_e32 v4, 0x3fb8aa3b, v4
	ds_read_b32 v5, v5
	v_exp_f32_e32 v4, v4
	s_waitcnt lgkmcnt(0)
	v_fmac_f32_e32 v3, v4, v5
	v_add_u32_e32 v5, 0x11e00, v2
	ds_write_b32 v5, v3
	v_add_u32_e32 v3, 0x12000, v2
	ds_write_b32 v3, v4
	v_add_u32_e32 v3, 0x11800, v2
	ds_read_b32 v3, v3
	v_add_u32_e32 v2, 0x12200, v2
	s_waitcnt lgkmcnt(0)
	v_add_f32_e32 v1, v1, v3
	v_mul_f32_e32 v1, 0xbfb8aa3b, v1
	v_exp_f32_e32 v1, v1
	ds_write_b32 v2, v1

.LBB0_1057:
	s_or_b64 exec, exec, s[68:69]
	v_add_f32_e32 v7, 0, v4
	v_add_f32_e32 v7, v7, v3
	v_add_f32_e32 v7, v7, v6
	v_add_f32_e32 v7, v7, v5
	v_cvt_pk_bf16_f32 v4, v4, v3
	v_mov_b32_e32 v3, v7
	v_mov_b32_e32 v255, v7
	s_nop 1
	v_permlane16_swap_b32_e32 v3, v255
	v_cvt_pk_bf16_f32 v5, v6, v5
	ds_write_b64 v0, v[4:5] offset:39984
	s_waitcnt lgkmcnt(1)
	v_add_f32_e32 v3, v3, v255
	s_nop 1
	v_mov_b32_dpp v4, v3 row_ror:8 row_mask:0xf bank_mask:0xf
	s_waitcnt lgkmcnt(0)
	v_add_f32_e32 v3, v3, v4
	s_nop 1
	v_mov_b32_dpp v4, v3 row_shl:4 row_mask:0xf bank_mask:0x5
	v_mov_b32_dpp v4, v3 row_shr:4 row_mask:0xf bank_mask:0xa
	s_nop 0
	v_add_f32_e32 v3, v3, v4
	s_nop 1
	v_mov_b32_dpp v4, v3 quad_perm:[2,3,0,1] row_mask:0xf bank_mask:0xf
	s_nop 0
	v_add_f32_e32 v3, v3, v4
	s_nop 1
	v_mov_b32_dpp v4, v3 quad_perm:[1,0,3,2] row_mask:0xf bank_mask:0xf
	s_and_saveexec_b64 s[0:1], vcc
	s_cbranch_execz .LBB0_1059
	v_lshl_add_u32 v2, v2, 2, 0
	s_waitcnt lgkmcnt(0)
	v_add_f32_e32 v3, v3, v4
	s_waitcnt vmcnt(0)
	v_sub_f32_e32 v4, v96, v1
	v_add_u32_e32 v5, 0x11c00, v2
	v_mul_f32_e32 v4, 0x3fb8aa3b, v4
	ds_read_b32 v5, v5
	v_exp_f32_e32 v4, v4
	s_waitcnt lgkmcnt(0)
	v_fmac_f32_e32 v3, v4, v5
	v_add_u32_e32 v5, 0x11e00, v2
	ds_write_b32 v5, v3
	v_add_u32_e32 v3, 0x12000, v2
	ds_write_b32 v3, v4
	v_add_u32_e32 v3, 0x11800, v2
	ds_read_b32 v3, v3
	v_add_u32_e32 v2, 0x12200, v2
	s_waitcnt lgkmcnt(0)
	v_add_f32_e32 v1, v1, v3
	v_mul_f32_e32 v1, 0xbfb8aa3b, v1
	v_exp_f32_e32 v1, v1
	ds_write_b32 v2, v1

.LBB0_1067:
	s_or_b64 exec, exec, s[68:69]
	v_add_f32_e32 v7, 0, v4
	v_add_f32_e32 v7, v7, v3
	v_add_f32_e32 v7, v7, v6
	v_add_f32_e32 v7, v7, v5
	v_cvt_pk_bf16_f32 v4, v4, v3
	v_mov_b32_e32 v3, v7
	v_mov_b32_e32 v255, v7
	s_nop 1
	v_permlane16_swap_b32_e32 v3, v255
	v_cvt_pk_bf16_f32 v5, v6, v5
	ds_write_b64 v0, v[4:5] offset:41344
	s_waitcnt lgkmcnt(1)
	v_add_f32_e32 v3, v3, v255
	s_nop 1
	v_mov_b32_dpp v4, v3 row_ror:8 row_mask:0xf bank_mask:0xf
	s_waitcnt lgkmcnt(0)
	v_add_f32_e32 v3, v3, v4
	s_nop 1
	v_mov_b32_dpp v4, v3 row_shl:4 row_mask:0xf bank_mask:0x5
	v_mov_b32_dpp v4, v3 row_shr:4 row_mask:0xf bank_mask:0xa
	s_nop 0
	v_add_f32_e32 v3, v3, v4
	s_nop 1
	v_mov_b32_dpp v4, v3 quad_perm:[2,3,0,1] row_mask:0xf bank_mask:0xf
	s_nop 0
	v_add_f32_e32 v3, v3, v4
	s_nop 1
	v_mov_b32_dpp v4, v3 quad_perm:[1,0,3,2] row_mask:0xf bank_mask:0xf
	s_and_saveexec_b64 s[0:1], vcc
	s_cbranch_execz .LBB0_1069
	v_lshl_add_u32 v2, v2, 2, 0
	s_waitcnt lgkmcnt(0)
	v_add_f32_e32 v3, v3, v4
	s_waitcnt vmcnt(0)
	v_sub_f32_e32 v4, v96, v1
	v_add_u32_e32 v5, 0x11c00, v2
	v_mul_f32_e32 v4, 0x3fb8aa3b, v4
	ds_read_b32 v5, v5
	v_exp_f32_e32 v4, v4
	s_waitcnt lgkmcnt(0)
	v_fmac_f32_e32 v3, v4, v5
	v_add_u32_e32 v5, 0x11e00, v2
	ds_write_b32 v5, v3
	v_add_u32_e32 v3, 0x12000, v2
	ds_write_b32 v3, v4
	v_add_u32_e32 v3, 0x11800, v2
	ds_read_b32 v3, v3
	v_add_u32_e32 v2, 0x12200, v2
	s_waitcnt lgkmcnt(0)
	v_add_f32_e32 v1, v1, v3
	v_mul_f32_e32 v1, 0xbfb8aa3b, v1
	v_exp_f32_e32 v1, v1
	ds_write_b32 v2, v1

.LBB0_1077:
	s_or_b64 exec, exec, s[68:69]
	v_add_f32_e32 v7, 0, v4
	v_add_f32_e32 v7, v7, v3
	v_add_f32_e32 v7, v7, v6
	v_add_f32_e32 v7, v7, v5
	v_cvt_pk_bf16_f32 v4, v4, v3
	v_mov_b32_e32 v3, v7
	v_mov_b32_e32 v255, v7
	s_nop 1
	v_permlane16_swap_b32_e32 v3, v255
	v_cvt_pk_bf16_f32 v5, v6, v5
	ds_write_b64 v0, v[4:5] offset:41616
	s_waitcnt lgkmcnt(1)
	v_add_f32_e32 v3, v3, v255
	s_nop 1
	v_mov_b32_dpp v4, v3 row_ror:8 row_mask:0xf bank_mask:0xf
	s_waitcnt lgkmcnt(0)
	v_add_f32_e32 v3, v3, v4
	s_nop 1
	v_mov_b32_dpp v4, v3 row_shl:4 row_mask:0xf bank_mask:0x5
	v_mov_b32_dpp v4, v3 row_shr:4 row_mask:0xf bank_mask:0xa
	s_nop 0
	v_add_f32_e32 v3, v3, v4
	s_nop 1
	v_mov_b32_dpp v4, v3 quad_perm:[2,3,0,1] row_mask:0xf bank_mask:0xf
	s_nop 0
	v_add_f32_e32 v3, v3, v4
	s_nop 1
	v_mov_b32_dpp v4, v3 quad_perm:[1,0,3,2] row_mask:0xf bank_mask:0xf
	s_and_saveexec_b64 s[0:1], vcc
	s_cbranch_execz .LBB0_1079
	v_lshl_add_u32 v2, v2, 2, 0
	s_waitcnt lgkmcnt(0)
	v_add_f32_e32 v3, v3, v4
	s_waitcnt vmcnt(0)
	v_sub_f32_e32 v4, v96, v1
	v_add_u32_e32 v5, 0x11c00, v2
	v_mul_f32_e32 v4, 0x3fb8aa3b, v4
	ds_read_b32 v5, v5
	v_exp_f32_e32 v4, v4
	s_waitcnt lgkmcnt(0)
	v_fmac_f32_e32 v3, v4, v5
	v_add_u32_e32 v5, 0x11e00, v2
	ds_write_b32 v5, v3
	v_add_u32_e32 v3, 0x12000, v2
	ds_write_b32 v3, v4
	v_add_u32_e32 v3, 0x11800, v2
	ds_read_b32 v3, v3
	v_add_u32_e32 v2, 0x12200, v2
	s_waitcnt lgkmcnt(0)
	v_add_f32_e32 v1, v1, v3
	v_mul_f32_e32 v1, 0xbfb8aa3b, v1
	v_exp_f32_e32 v1, v1
	ds_write_b32 v2, v1

.LBB0_1087:
	s_or_b64 exec, exec, s[68:69]
	v_add_f32_e32 v7, 0, v4
	v_add_f32_e32 v7, v7, v3
	v_add_f32_e32 v7, v7, v6
	v_add_f32_e32 v7, v7, v5
	v_cvt_pk_bf16_f32 v4, v4, v3
	v_mov_b32_e32 v3, v7
	v_mov_b32_e32 v255, v7
	s_nop 1
	v_permlane16_swap_b32_e32 v3, v255
	v_cvt_pk_bf16_f32 v5, v6, v5
	ds_write_b64 v0, v[4:5] offset:41888
	s_waitcnt lgkmcnt(1)
	v_add_f32_e32 v3, v3, v255
	s_nop 1
	v_mov_b32_dpp v4, v3 row_ror:8 row_mask:0xf bank_mask:0xf
	s_waitcnt lgkmcnt(0)
	v_add_f32_e32 v3, v3, v4
	s_nop 1
	v_mov_b32_dpp v4, v3 row_shl:4 row_mask:0xf bank_mask:0x5
	v_mov_b32_dpp v4, v3 row_shr:4 row_mask:0xf bank_mask:0xa
	s_nop 0
	v_add_f32_e32 v3, v3, v4
	s_nop 1
	v_mov_b32_dpp v4, v3 quad_perm:[2,3,0,1] row_mask:0xf bank_mask:0xf
	s_nop 0
	v_add_f32_e32 v3, v3, v4
	s_nop 1
	v_mov_b32_dpp v4, v3 quad_perm:[1,0,3,2] row_mask:0xf bank_mask:0xf
	s_and_saveexec_b64 s[0:1], vcc
	s_cbranch_execz .LBB0_1089
	v_lshl_add_u32 v2, v2, 2, 0
	s_waitcnt lgkmcnt(0)
	v_add_f32_e32 v3, v3, v4
	s_waitcnt vmcnt(0)
	v_sub_f32_e32 v4, v96, v1
	v_add_u32_e32 v5, 0x11c00, v2
	v_mul_f32_e32 v4, 0x3fb8aa3b, v4
	ds_read_b32 v5, v5
	v_exp_f32_e32 v4, v4
	s_waitcnt lgkmcnt(0)
	v_fmac_f32_e32 v3, v4, v5
	v_add_u32_e32 v5, 0x11e00, v2
	ds_write_b32 v5, v3
	v_add_u32_e32 v3, 0x12000, v2
	ds_write_b32 v3, v4
	v_add_u32_e32 v3, 0x11800, v2
	ds_read_b32 v3, v3
	v_add_u32_e32 v2, 0x12200, v2
	s_waitcnt lgkmcnt(0)
	v_add_f32_e32 v1, v1, v3
	v_mul_f32_e32 v1, 0xbfb8aa3b, v1
	v_exp_f32_e32 v1, v1
	ds_write_b32 v2, v1

.LBB0_1097:
	s_or_b64 exec, exec, s[6:7]
	v_add_f32_e32 v7, 0, v4
	v_add_f32_e32 v7, v7, v3
	v_add_f32_e32 v7, v7, v6
	v_add_f32_e32 v7, v7, v5
	v_cvt_pk_bf16_f32 v4, v4, v3
	v_cvt_pk_bf16_f32 v5, v6, v5
	ds_write_b64 v0, v[4:5] offset:42160
	v_mov_b32_e32 v0, v7
	v_mov_b32_e32 v255, v7
	s_nop 1
	v_permlane16_swap_b32_e32 v0, v255
	s_waitcnt lgkmcnt(0)
	v_add_f32_e32 v0, v0, v255
	s_nop 1
	v_mov_b32_dpp v3, v0 row_ror:8 row_mask:0xf bank_mask:0xf
	s_nop 0
	v_add_f32_e32 v0, v0, v3
	s_nop 1
	v_mov_b32_dpp v3, v0 row_shl:4 row_mask:0xf bank_mask:0x5
	v_mov_b32_dpp v3, v0 row_shr:4 row_mask:0xf bank_mask:0xa
	s_nop 0
	v_add_f32_e32 v0, v0, v3
	s_nop 1
	v_mov_b32_dpp v3, v0 quad_perm:[2,3,0,1] row_mask:0xf bank_mask:0xf
	s_nop 0
	v_add_f32_e32 v0, v0, v3
	s_nop 1
	v_mov_b32_dpp v3, v0 quad_perm:[1,0,3,2] row_mask:0xf bank_mask:0xf
	s_and_saveexec_b64 s[0:1], vcc
	s_cbranch_execz .LBB0_1099
	v_lshl_add_u32 v2, v2, 2, 0
	s_waitcnt lgkmcnt(0)
	v_add_f32_e32 v0, v0, v3
	s_waitcnt vmcnt(0)
	v_sub_f32_e32 v3, v96, v1
	v_add_u32_e32 v4, 0x11c00, v2
	v_mul_f32_e32 v3, 0x3fb8aa3b, v3
	ds_read_b32 v4, v4
	v_exp_f32_e32 v3, v3
	s_waitcnt lgkmcnt(0)
	v_fmac_f32_e32 v0, v3, v4
	v_add_u32_e32 v4, 0x11e00, v2
	ds_write_b32 v4, v0
	v_add_u32_e32 v0, 0x12000, v2
	ds_write_b32 v0, v3
	v_add_u32_e32 v0, 0x11800, v2
	ds_read_b32 v0, v0
	s_waitcnt lgkmcnt(0)
	v_add_f32_e32 v0, v1, v0
	v_mul_f32_e32 v0, 0xbfb8aa3b, v0
	v_exp_f32_e32 v0, v0
	v_add_u32_e32 v1, 0x12200, v2
	ds_write_b32 v1, v0

.LBB0_1107:
	ds_read_b128 v[100:103], v98
	ds_read_b128 v[104:107], v96
	s_add_i32 s0, s0, 32
	s_cmpk_lt_u32 s0, 0x70
	s_waitcnt lgkmcnt(0)
	v_mfma_f32_32x32x16_bf16 v[0:15], v[100:103], v[104:107], v[0:15]
	ds_read_b128 v[104:107], v96 offset:8704
	s_waitcnt lgkmcnt(0)
	v_mfma_f32_32x32x16_bf16 v[16:31], v[100:103], v[104:107], v[16:31]
	ds_read_b128 v[104:107], v96 offset:17408
	s_waitcnt lgkmcnt(0)
	v_mfma_f32_32x32x16_bf16 v[32:47], v[100:103], v[104:107], v[32:47]
	ds_read_b128 v[104:107], v96 offset:26112
	s_waitcnt lgkmcnt(0)
	v_mfma_f32_32x32x16_bf16 v[48:63], v[100:103], v[104:107], v[48:63]
	ds_read_b128 v[100:103], v98 offset:32
	ds_read_b128 v[104:107], v96 offset:32
	v_add_u32_e32 v98, 64, v98
	s_waitcnt lgkmcnt(0)
	v_mfma_f32_32x32x16_bf16 v[0:15], v[100:103], v[104:107], v[0:15]
	ds_read_b128 v[104:107], v96 offset:8736
	s_waitcnt lgkmcnt(0)
	v_mfma_f32_32x32x16_bf16 v[16:31], v[100:103], v[104:107], v[16:31]
	ds_read_b128 v[104:107], v96 offset:17440
	s_waitcnt lgkmcnt(0)
	v_mfma_f32_32x32x16_bf16 v[32:47], v[100:103], v[104:107], v[32:47]
	ds_read_b128 v[104:107], v96 offset:26144
	v_add_u32_e32 v96, 64, v96
	s_waitcnt lgkmcnt(0)
	v_mfma_f32_32x32x16_bf16 v[48:63], v[100:103], v[104:107], v[48:63]
	s_cbranch_scc1 .LBB0_1107
	v_mov_b32_e32 v96, v128
	s_mov_b64 s[0:1], -1
	v_ashrrev_i32_e32 v98, 3, v96
	v_and_b32_e32 v98, -4, v98
	v_and_b32_e32 v103, 31, v96
	v_add_u32_e32 v105, v98, v129
	v_lshlrev_b32_e32 v96, 2, v103
	v_lshl_add_u64 v[98:99], s[56:57], 0, v[96:97]
	v_add_u32_e32 v100, s61, v105
	v_or_b32_e32 v96, 1, v105
	v_or_b32_e32 v102, 2, v105
	s_andn2_b64 vcc, exec, s[54:55]
	v_lshlrev_b32_e32 v237, 2, v105
	v_ashrrev_i32_e32 v101, 31, v100
	v_lshlrev_b32_e32 v236, 2, v96
	v_add_u32_e32 v104, s61, v96
	v_lshlrev_b32_e32 v235, 2, v102
	v_add_u32_e32 v102, s61, v102
	v_or_b32_e32 v234, 3, v105
	s_cbranch_vccnz .LBB0_1110
	s_add_i32 s0, 0, 0x11e00
	s_add_i32 s1, 0, 0x12200
	v_add_u32_e32 v238, s0, v237
	v_add_u32_e32 v239, s1, v237
	ds_read_b32 v96, v238
	ds_read_b32 v105, v239
	v_mov_b32_e32 v110, v0
	v_mov_b32_e32 v111, v16
	v_or_b32_e32 v103, s75, v103
	s_waitcnt lgkmcnt(1)
	v_max_f32_e64 v96, |v96|, |v96|
	s_waitcnt lgkmcnt(0)
	v_max_f32_e32 v105, v105, v105
	v_max_f32_e32 v96, v96, v105
	v_div_scale_f32 v105, s[6:7], v96, v96, 1.0
	v_rcp_f32_e32 v106, v105
	v_readlane_b32 s6, v249, 7
	v_readlane_b32 s7, v249, 8
	v_readlane_b32 s12, v251, 20
	v_fma_f32 v107, -v105, v106, 1.0
	v_fmac_f32_e32 v106, v107, v106
	v_div_scale_f32 v107, vcc, 1.0, v96, 1.0
	v_mul_f32_e32 v108, v107, v106
	v_fma_f32 v109, -v105, v108, v107
	v_fmac_f32_e32 v108, v109, v106
	v_fma_f32 v105, -v105, v108, v107
	v_div_fmas_f32 v105, v105, v106, v108
	v_lshlrev_b64 v[106:107], 11, v[100:101]
	v_lshl_add_u64 v[106:107], v[98:99], 0, v[106:107]
	global_load_dword v108, v[106:107], off
	global_load_dword v109, v[106:107], off offset:128
	global_load_dword v112, v[106:107], off offset:256
	global_load_dword v113, v[106:107], off offset:384
	v_div_fixup_f32 v96, v105, v96, 1.0
	v_mov_b32_e32 v106, v32
	v_mov_b32_e32 v107, v48
	v_readlane_b32 s18, v251, 26
	v_readlane_b32 s19, v251, 27
	v_readlane_b32 s14, v251, 22
	v_readlane_b32 s15, v251, 23
	v_readlane_b32 s16, v251, 24
	v_readlane_b32 s17, v251, 25
	v_readlane_b32 s20, v251, 28
	v_readlane_b32 s21, v251, 29
	v_readlane_b32 s22, v251, 30
	v_readlane_b32 s23, v251, 31
	v_readlane_b32 s25, v251, 33
	v_readlane_b32 s14, v248, 4
	s_mov_b64 s[16:17], s[82:83]
	s_mov_b32 s25, 0x85000
	s_mov_b32 s23, 0x59000
	s_mov_b32 s22, 0x2d000
	s_mov_b32 s21, 0x84000
	s_mov_b32 s20, 0x58000
	s_movk_i32 s29, 0x47ff
	s_mov_b32 s28, 0x4800000
	v_readlane_b32 s15, v248, 5
	v_readlane_b32 s13, v251, 21
	v_readlane_b32 s24, v251, 32
	v_readlane_b32 s26, v251, 34
	v_readlane_b32 s27, v251, 35
	s_waitcnt vmcnt(2)
	v_pk_fma_f32 v[110:111], v[110:111], v[96:97], v[108:109] op_sel_hi:[1,0,1]
	v_pk_mul_f32 v[108:109], v[110:111], v[110:111]
	s_waitcnt vmcnt(0)
	v_pk_fma_f32 v[124:125], v[106:107], v[96:97], v[112:113] op_sel_hi:[1,0,1]
	v_add_f32_e32 v96, v108, v109
	v_pk_mul_f32 v[106:107], v[124:125], v[124:125]
	v_add_f32_e32 v96, v96, v106
	v_add_f32_e32 v96, v96, v107
	v_mov_b32_e32 v105, v96
	v_mov_b32_e32 v255, v96
	s_nop 1
	v_permlane16_swap_b32_e32 v105, v255
	s_nop 1
	v_mov_b32_dpp v105, v255 quad_perm:[0,1,2,3] row_mask:0x5 bank_mask:0xf
	v_mov_b64_e32 v[106:107], s[6:7]
	v_mad_i64_i32 v[108:109], s[6:7], v100, s74, v[106:107]
	v_lshl_add_u64 v[126:127], v[108:109], 0, s[96:97]
	v_add_f32_e32 v96, v96, v105
	s_nop 1
	v_mov_b32_dpp v105, v96 row_ror:8 row_mask:0xf bank_mask:0xf
	v_lshlrev_b64 v[108:109], 10, v[100:101]
	v_lshl_add_u64 v[112:113], s[66:67], 0, v[108:109]
	v_add_f32_e32 v96, v96, v105
	s_nop 1
	v_mov_b32_dpp v105, v96 row_shl:4 row_mask:0xf bank_mask:0x5
	v_mov_b32_dpp v105, v96 row_shr:4 row_mask:0xf bank_mask:0xa
	s_nop 0
	v_add_f32_e32 v96, v96, v105
	s_nop 1
	v_mov_b32_dpp v105, v96 quad_perm:[2,3,0,1] row_mask:0xf bank_mask:0xf
	v_add_f32_e32 v96, v96, v105
	s_nop 1
	v_add_f32_dpp v96, v96, v96 quad_perm:[1,0,3,2] row_mask:0xf bank_mask:0xf
	v_fmamk_f32 v96, v96, 0x3c000000, v163
	v_cmp_gt_f32_e32 vcc, s86, v96
	v_mul_f32_e32 v105, 0x4b800000, v96
	s_nop 0
	v_cndmask_b32_e32 v96, v96, v105, vcc
	v_rsq_f32_e32 v96, v96
	s_nop 0
	v_mul_f32_e32 v105, 0x45800000, v96
	v_cndmask_b32_e32 v105, v96, v105, vcc
	v_lshlrev_b32_e32 v96, 1, v103
	v_lshl_add_u64 v[108:109], v[126:127], 0, v[96:97]
	global_load_ushort v108, v[108:109], off
	v_mov_b32_e32 v109, v97
	v_mul_f32_e32 v110, v110, v105
	v_lshl_add_u64 v[122:123], v[112:113], 0, v[96:97]
	v_or_b32_e32 v112, 64, v96
	v_mov_b32_e32 v113, v97
	s_waitcnt vmcnt(0)
	v_lshlrev_b32_e32 v108, 16, v108
	v_mul_f32_e32 v108, 0xbfb8aa3b, v108
	v_exp_f32_e32 v108, v108
	s_nop 0
	v_add_f32_e32 v108, 1.0, v108
	v_rcp_f32_e32 v118, v108
	v_or_b32_e32 v108, s34, v103
	v_lshl_add_u64 v[108:109], v[108:109], 2, s[18:19]
	global_load_dword v119, v[108:109], off
	s_waitcnt vmcnt(0)
	v_mul_f32_e32 v110, v119, v110
	v_mul_f32_e32 v110, v118, v110
	v_cvt_pk_bf16_f32 v110, v110, s0
	v_lshl_add_u64 v[118:119], v[126:127], 0, v[112:113]
	global_store_short v[122:123], v110, off
	global_load_ushort v110, v[118:119], off
	v_mul_f32_e32 v119, v111, v105
	v_mov_b32_e32 v111, v97
	s_waitcnt vmcnt(0)
	v_lshlrev_b32_e32 v110, 16, v110
	v_mul_f32_e32 v110, 0xbfb8aa3b, v110
	v_exp_f32_e32 v110, v110
	s_nop 0
	v_add_f32_e32 v110, 1.0, v110
	v_rcp_f32_e32 v118, v110
	v_add_u32_e32 v110, s34, v103
	v_lshl_add_u64 v[110:111], v[110:111], 2, s[18:19]
	global_load_dword v103, v[110:111], off offset:128
	s_mov_b32 s19, 0x2c000
	s_movk_i32 s18, 0x1600
	s_waitcnt vmcnt(0)
	v_mul_f32_e32 v103, v103, v119
	v_mul_f32_e32 v103, v118, v103
	v_or_b32_e32 v118, 0x80, v96
	v_mov_b32_e32 v119, v97
	v_cvt_pk_bf16_f32 v103, v103, s0
	v_lshl_add_u64 v[120:121], v[126:127], 0, v[118:119]
	global_store_short v[122:123], v103, off offset:64
	global_load_ushort v103, v[120:121], off
	v_mul_f32_e32 v120, v124, v105
	global_load_dword v121, v[110:111], off offset:256
	global_load_dword v124, v[110:111], off offset:384
	v_mul_f32_e32 v105, v125, v105
	s_waitcnt vmcnt(2)
	v_lshlrev_b32_e32 v103, 16, v103
	v_mul_f32_e32 v103, 0xbfb8aa3b, v103
	v_exp_f32_e32 v103, v103
	s_waitcnt vmcnt(1)
	v_mul_f32_e32 v120, v121, v120
	v_mov_b32_e32 v121, v97
	s_waitcnt vmcnt(0)
	v_mul_f32_e32 v105, v124, v105
	v_add_f32_e32 v103, 1.0, v103
	v_rcp_f32_e32 v103, v103
	s_nop 0
	v_mul_f32_e32 v103, v120, v103
	v_or_b32_e32 v120, 0xc0, v96
	v_cvt_pk_bf16_f32 v103, v103, s0
	v_lshl_add_u64 v[126:127], v[126:127], 0, v[120:121]
	global_store_short v[122:123], v103, off offset:128
	global_load_ushort v103, v[126:127], off
	s_waitcnt vmcnt(0)
	v_lshlrev_b32_e32 v103, 16, v103
	v_mul_f32_e32 v103, 0xbfb8aa3b, v103
	v_exp_f32_e32 v103, v103
	s_nop 0
	v_add_f32_e32 v103, 1.0, v103
	v_rcp_f32_e32 v103, v103
	s_nop 0
	v_mul_f32_e32 v103, v105, v103
	v_cvt_pk_bf16_f32 v103, v103, s0
	global_store_short v[122:123], v103, off offset:192
	v_add_u32_e32 v103, s0, v236
	v_add_u32_e32 v105, s1, v236
	ds_read_b32 v103, v103
	ds_read_b32 v105, v105
	v_mov_b32_e32 v242, v1
	v_mov_b32_e32 v243, v17
	s_waitcnt lgkmcnt(1)
	v_max_f32_e64 v103, |v103|, |v103|
	s_waitcnt lgkmcnt(0)
	v_max_f32_e32 v105, v105, v105
	v_max_f32_e32 v103, v103, v105
	v_div_scale_f32 v105, s[6:7], v103, v103, 1.0
	v_rcp_f32_e32 v122, v105
	s_nop 0
	v_fma_f32 v123, -v105, v122, 1.0
	v_fmac_f32_e32 v122, v123, v122
	v_div_scale_f32 v123, vcc, 1.0, v103, 1.0
	v_mul_f32_e32 v124, v123, v122
	v_fma_f32 v125, -v105, v124, v123
	v_fmac_f32_e32 v124, v125, v122
	v_fma_f32 v105, -v105, v124, v123
	v_div_fmas_f32 v105, v105, v122, v124
	v_div_fixup_f32 v122, v105, v103, 1.0
	v_ashrrev_i32_e32 v105, 31, v104
	v_lshlrev_b64 v[124:125], 11, v[104:105]
	v_lshl_add_u64 v[124:125], v[98:99], 0, v[124:125]
	global_load_dword v126, v[124:125], off
	global_load_dword v127, v[124:125], off offset:128
	global_load_dword v244, v[124:125], off offset:256
	global_load_dword v245, v[124:125], off offset:384
	v_mov_b32_e32 v124, v33
	v_mov_b32_e32 v125, v49
	s_waitcnt vmcnt(2)
	v_pk_fma_f32 v[126:127], v[242:243], v[122:123], v[126:127] op_sel_hi:[1,0,1]
	v_pk_mul_f32 v[242:243], v[126:127], v[126:127]
	s_waitcnt vmcnt(0)
	v_pk_fma_f32 v[124:125], v[124:125], v[122:123], v[244:245] op_sel_hi:[1,0,1]
	v_add_f32_e32 v103, v242, v243
	v_pk_mul_f32 v[122:123], v[124:125], v[124:125]
	v_add_f32_e32 v103, v103, v122
	v_add_f32_e32 v103, v103, v123
	v_mov_b32_e32 v122, v103
	v_mov_b32_e32 v255, v103
	s_nop 1
	v_permlane16_swap_b32_e32 v122, v255
	s_nop 1
	v_mov_b32_dpp v122, v255 quad_perm:[0,1,2,3] row_mask:0x5 bank_mask:0xf
	s_nop 0
	v_add_f32_e32 v103, v103, v122
	s_nop 1
	v_mov_b32_dpp v122, v103 row_ror:8 row_mask:0xf bank_mask:0xf
	s_nop 0
	v_add_f32_e32 v103, v103, v122
	s_nop 1
	v_mov_b32_dpp v122, v103 row_shl:4 row_mask:0xf bank_mask:0x5
	v_mov_b32_dpp v122, v103 row_shr:4 row_mask:0xf bank_mask:0xa
	s_nop 0
	v_add_f32_e32 v103, v103, v122
	s_nop 1
	v_mov_b32_dpp v122, v103 quad_perm:[2,3,0,1] row_mask:0xf bank_mask:0xf
	v_add_f32_e32 v103, v103, v122
	s_nop 1
	v_add_f32_dpp v103, v103, v103 quad_perm:[1,0,3,2] row_mask:0xf bank_mask:0xf
	v_fmamk_f32 v103, v103, 0x3c000000, v163
	v_cmp_gt_f32_e32 vcc, s86, v103
	v_mul_f32_e32 v122, 0x4b800000, v103
	s_nop 0
	v_cndmask_b32_e32 v103, v103, v122, vcc
	v_rsq_f32_e32 v103, v103
	s_nop 0
	v_mul_f32_e32 v122, 0x45800000, v103
	v_cndmask_b32_e32 v103, v103, v122, vcc
	v_mad_i64_i32 v[122:123], s[6:7], v104, s74, v[106:107]
	v_lshl_add_u64 v[242:243], v[122:123], 0, s[96:97]
	v_lshl_add_u64 v[244:245], v[242:243], 0, v[96:97]
	v_lshlrev_b64 v[122:123], 10, v[104:105]
	global_load_ushort v105, v[244:245], off
	v_mul_f32_e32 v126, v126, v103
	global_load_dword v244, v[108:109], off
	v_lshl_add_u64 v[122:123], s[66:67], 0, v[122:123]
	v_lshl_add_u64 v[122:123], v[122:123], 0, v[96:97]
	v_mul_f32_e32 v124, v124, v103
	s_waitcnt vmcnt(1)
	v_lshlrev_b32_e32 v105, 16, v105
	v_mul_f32_e32 v105, 0xbfb8aa3b, v105
	v_exp_f32_e32 v105, v105
	s_waitcnt vmcnt(0)
	v_mul_f32_e32 v126, v244, v126
	v_lshl_add_u64 v[244:245], v[242:243], 0, v[112:113]
	v_add_f32_e32 v105, 1.0, v105
	v_rcp_f32_e32 v105, v105
	s_nop 0
	v_mul_f32_e32 v105, v105, v126
	v_cvt_pk_bf16_f32 v105, v105, s0
	global_store_short v[122:123], v105, off
	global_load_ushort v105, v[244:245], off
	v_mul_f32_e32 v126, v127, v103
	global_load_dword v127, v[110:111], off offset:128
	v_mul_f32_e32 v103, v125, v103
	s_waitcnt vmcnt(1)
	v_lshlrev_b32_e32 v105, 16, v105
	v_mul_f32_e32 v105, 0xbfb8aa3b, v105
	v_exp_f32_e32 v105, v105
	s_waitcnt vmcnt(0)
	v_mul_f32_e32 v126, v127, v126
	v_add_f32_e32 v105, 1.0, v105
	v_rcp_f32_e32 v105, v105
	s_nop 0
	v_mul_f32_e32 v105, v105, v126
	v_cvt_pk_bf16_f32 v105, v105, s0
	v_lshl_add_u64 v[126:127], v[242:243], 0, v[118:119]
	global_store_short v[122:123], v105, off offset:64
	global_load_ushort v105, v[126:127], off
	s_waitcnt vmcnt(0)
	v_lshlrev_b32_e32 v105, 16, v105
	global_load_dword v126, v[110:111], off offset:256
	v_mul_f32_e32 v105, 0xbfb8aa3b, v105
	v_exp_f32_e32 v105, v105
	s_waitcnt vmcnt(0)
	v_mul_f32_e32 v124, v126, v124
	v_add_f32_e32 v105, 1.0, v105
	v_rcp_f32_e32 v105, v105
	v_lshl_add_u64 v[126:127], v[242:243], 0, v[120:121]
	v_mul_f32_e32 v105, v124, v105
	v_cvt_pk_bf16_f32 v105, v105, s0
	global_store_short v[122:123], v105, off offset:128
	global_load_ushort v105, v[126:127], off
	s_waitcnt vmcnt(0)
	v_lshlrev_b32_e32 v105, 16, v105
	global_load_dword v124, v[110:111], off offset:384
	v_mul_f32_e32 v105, 0xbfb8aa3b, v105
	v_exp_f32_e32 v105, v105
	s_waitcnt vmcnt(0)
	v_mul_f32_e32 v103, v124, v103
	v_add_f32_e32 v105, 1.0, v105
	v_rcp_f32_e32 v105, v105
	s_nop 0
	v_mul_f32_e32 v103, v103, v105
	v_cvt_pk_bf16_f32 v103, v103, s0
	global_store_short v[122:123], v103, off offset:192
	v_add_u32_e32 v103, s0, v235
	v_add_u32_e32 v105, s1, v235
	ds_read_b32 v103, v103
	ds_read_b32 v105, v105
	v_mov_b32_e32 v242, v2
	v_mov_b32_e32 v243, v18
	s_waitcnt lgkmcnt(1)
	v_max_f32_e64 v103, |v103|, |v103|
	s_waitcnt lgkmcnt(0)
	v_max_f32_e32 v105, v105, v105
	v_max_f32_e32 v103, v103, v105
	v_div_scale_f32 v105, s[6:7], v103, v103, 1.0
	v_rcp_f32_e32 v122, v105
	s_nop 0
	v_fma_f32 v123, -v105, v122, 1.0
	v_fmac_f32_e32 v122, v123, v122
	v_div_scale_f32 v123, vcc, 1.0, v103, 1.0
	v_mul_f32_e32 v124, v123, v122
	v_fma_f32 v125, -v105, v124, v123
	v_fmac_f32_e32 v124, v125, v122
	v_fma_f32 v105, -v105, v124, v123
	v_div_fmas_f32 v105, v105, v122, v124
	v_div_fixup_f32 v122, v105, v103, 1.0
	v_ashrrev_i32_e32 v103, 31, v102
	v_lshlrev_b64 v[124:125], 11, v[102:103]
	v_lshl_add_u64 v[124:125], v[98:99], 0, v[124:125]
	global_load_dword v126, v[124:125], off
	global_load_dword v127, v[124:125], off offset:128
	global_load_dword v244, v[124:125], off offset:256
	global_load_dword v245, v[124:125], off offset:384
	v_mov_b32_e32 v124, v34
	v_mov_b32_e32 v125, v50
	s_waitcnt vmcnt(2)
	v_pk_fma_f32 v[126:127], v[242:243], v[122:123], v[126:127] op_sel_hi:[1,0,1]
	v_pk_mul_f32 v[242:243], v[126:127], v[126:127]
	s_waitcnt vmcnt(0)
	v_pk_fma_f32 v[124:125], v[124:125], v[122:123], v[244:245] op_sel_hi:[1,0,1]
	v_add_f32_e32 v105, v242, v243
	v_pk_mul_f32 v[122:123], v[124:125], v[124:125]
	v_add_f32_e32 v105, v105, v122
	v_add_f32_e32 v105, v105, v123
	v_mov_b32_e32 v122, v105
	v_mov_b32_e32 v255, v105
	s_nop 1
	v_permlane16_swap_b32_e32 v122, v255
	s_nop 1
	v_mov_b32_dpp v122, v255 quad_perm:[0,1,2,3] row_mask:0x5 bank_mask:0xf
	s_nop 0
	v_add_f32_e32 v105, v105, v122
	s_nop 1
	v_mov_b32_dpp v122, v105 row_ror:8 row_mask:0xf bank_mask:0xf
	s_nop 0
	v_add_f32_e32 v105, v105, v122
	s_nop 1
	v_mov_b32_dpp v122, v105 row_shl:4 row_mask:0xf bank_mask:0x5
	v_mov_b32_dpp v122, v105 row_shr:4 row_mask:0xf bank_mask:0xa
	s_nop 0
	v_add_f32_e32 v105, v105, v122
	s_nop 1
	v_mov_b32_dpp v122, v105 quad_perm:[2,3,0,1] row_mask:0xf bank_mask:0xf
	v_add_f32_e32 v105, v105, v122
	s_nop 1
	v_add_f32_dpp v105, v105, v105 quad_perm:[1,0,3,2] row_mask:0xf bank_mask:0xf
	v_fmamk_f32 v105, v105, 0x3c000000, v163
	v_cmp_gt_f32_e32 vcc, s86, v105
	v_mul_f32_e32 v122, 0x4b800000, v105
	s_nop 0
	v_cndmask_b32_e32 v105, v105, v122, vcc
	v_rsq_f32_e32 v105, v105
	s_nop 0
	v_mul_f32_e32 v122, 0x45800000, v105
	v_cndmask_b32_e32 v105, v105, v122, vcc
	v_mad_i64_i32 v[122:123], s[6:7], v102, s74, v[106:107]
	v_lshl_add_u64 v[242:243], v[122:123], 0, s[96:97]
	v_lshl_add_u64 v[244:245], v[242:243], 0, v[96:97]
	v_lshlrev_b64 v[122:123], 10, v[102:103]
	global_load_ushort v103, v[244:245], off
	v_mul_f32_e32 v126, v126, v105
	global_load_dword v244, v[108:109], off
	v_lshl_add_u64 v[122:123], s[66:67], 0, v[122:123]
	v_lshl_add_u64 v[122:123], v[122:123], 0, v[96:97]
	v_mul_f32_e32 v124, v124, v105
	s_waitcnt vmcnt(1)
	v_lshlrev_b32_e32 v103, 16, v103
	v_mul_f32_e32 v103, 0xbfb8aa3b, v103
	v_exp_f32_e32 v103, v103
	s_waitcnt vmcnt(0)
	v_mul_f32_e32 v126, v244, v126
	v_lshl_add_u64 v[244:245], v[242:243], 0, v[112:113]
	v_add_f32_e32 v103, 1.0, v103
	v_rcp_f32_e32 v103, v103
	s_nop 0
	v_mul_f32_e32 v103, v103, v126
	v_cvt_pk_bf16_f32 v103, v103, s0
	global_store_short v[122:123], v103, off
	global_load_ushort v103, v[244:245], off
	v_mul_f32_e32 v126, v127, v105
	global_load_dword v127, v[110:111], off offset:128
	v_mul_f32_e32 v105, v125, v105
	s_waitcnt vmcnt(1)
	v_lshlrev_b32_e32 v103, 16, v103
	v_mul_f32_e32 v103, 0xbfb8aa3b, v103
	v_exp_f32_e32 v103, v103
	s_waitcnt vmcnt(0)
	v_mul_f32_e32 v126, v127, v126
	v_add_f32_e32 v103, 1.0, v103
	v_rcp_f32_e32 v103, v103
	s_nop 0
	v_mul_f32_e32 v103, v103, v126
	v_cvt_pk_bf16_f32 v103, v103, s0
	v_lshl_add_u64 v[126:127], v[242:243], 0, v[118:119]
	global_store_short v[122:123], v103, off offset:64
	global_load_ushort v103, v[126:127], off
	s_waitcnt vmcnt(0)
	v_lshlrev_b32_e32 v103, 16, v103
	global_load_dword v126, v[110:111], off offset:256
	v_mul_f32_e32 v103, 0xbfb8aa3b, v103
	v_exp_f32_e32 v103, v103
	s_waitcnt vmcnt(0)
	v_mul_f32_e32 v124, v126, v124
	v_add_f32_e32 v103, 1.0, v103
	v_rcp_f32_e32 v103, v103
	v_lshl_add_u64 v[126:127], v[242:243], 0, v[120:121]
	v_mul_f32_e32 v103, v124, v103
	v_cvt_pk_bf16_f32 v103, v103, s0
	global_store_short v[122:123], v103, off offset:128
	global_load_ushort v103, v[126:127], off
	s_waitcnt vmcnt(0)
	v_lshlrev_b32_e32 v103, 16, v103
	global_load_dword v124, v[110:111], off offset:384
	v_mul_f32_e32 v103, 0xbfb8aa3b, v103
	v_exp_f32_e32 v103, v103
	s_waitcnt vmcnt(0)
	v_mul_f32_e32 v105, v124, v105
	v_add_f32_e32 v103, 1.0, v103
	v_rcp_f32_e32 v103, v103
	s_nop 0
	v_mul_f32_e32 v103, v105, v103
	v_cvt_pk_bf16_f32 v103, v103, s0
	global_store_short v[122:123], v103, off offset:192
	v_lshlrev_b32_e32 v103, 2, v234
	v_add_u32_e32 v105, s0, v103
	v_add_u32_e32 v103, s1, v103
	ds_read_b32 v105, v105
	ds_read_b32 v103, v103
	v_add_u32_e32 v126, s61, v234
	v_ashrrev_i32_e32 v127, 31, v126
	v_mov_b32_e32 v244, v3
	s_waitcnt lgkmcnt(1)
	v_max_f32_e64 v105, |v105|, |v105|
	s_waitcnt lgkmcnt(0)
	v_max_f32_e32 v103, v103, v103
	v_max_f32_e32 v103, v105, v103
	v_div_scale_f32 v105, s[0:1], v103, v103, 1.0
	v_rcp_f32_e32 v122, v105
	v_mov_b32_e32 v245, v19
	v_fma_f32 v123, -v105, v122, 1.0
	v_fmac_f32_e32 v122, v123, v122
	v_div_scale_f32 v123, vcc, 1.0, v103, 1.0
	v_mul_f32_e32 v124, v123, v122
	v_fma_f32 v125, -v105, v124, v123
	v_fmac_f32_e32 v124, v125, v122
	v_fma_f32 v105, -v105, v124, v123
	v_div_fmas_f32 v105, v105, v122, v124
	v_lshlrev_b64 v[124:125], 11, v[126:127]
	v_lshl_add_u64 v[124:125], v[98:99], 0, v[124:125]
	global_load_dword v242, v[124:125], off
	global_load_dword v243, v[124:125], off offset:128
	global_load_dword v246, v[124:125], off offset:256
	global_load_dword v247, v[124:125], off offset:384
	v_div_fixup_f32 v122, v105, v103, 1.0
	v_mov_b32_e32 v124, v35
	v_mov_b32_e32 v125, v51
	s_waitcnt vmcnt(2)
	v_pk_fma_f32 v[242:243], v[244:245], v[122:123], v[242:243] op_sel_hi:[1,0,1]
	v_pk_mul_f32 v[244:245], v[242:243], v[242:243]
	s_waitcnt vmcnt(0)
	v_pk_fma_f32 v[124:125], v[124:125], v[122:123], v[246:247] op_sel_hi:[1,0,1]
	v_add_f32_e32 v103, v244, v245
	v_pk_mul_f32 v[122:123], v[124:125], v[124:125]
	v_add_f32_e32 v103, v103, v122
	v_add_f32_e32 v103, v103, v123
	v_mov_b32_e32 v105, v103
	v_mov_b32_e32 v255, v103
	s_nop 1
	v_permlane16_swap_b32_e32 v105, v255
	s_nop 1
	v_mov_b32_dpp v105, v255 quad_perm:[0,1,2,3] row_mask:0x5 bank_mask:0xf
	v_mad_i64_i32 v[122:123], s[0:1], v126, s74, v[106:107]
	v_lshl_add_u64 v[244:245], v[122:123], 0, s[96:97]
	v_lshlrev_b64 v[122:123], 10, v[126:127]
	v_add_f32_e32 v103, v103, v105
	s_nop 1
	v_mov_b32_dpp v105, v103 row_ror:8 row_mask:0xf bank_mask:0xf
	v_lshl_add_u64 v[126:127], v[244:245], 0, v[96:97]
	v_lshl_add_u64 v[122:123], s[66:67], 0, v[122:123]
	v_lshl_add_u64 v[122:123], v[122:123], 0, v[96:97]
	v_add_f32_e32 v103, v103, v105
	s_nop 1
	v_mov_b32_dpp v105, v103 row_shl:4 row_mask:0xf bank_mask:0x5
	v_mov_b32_dpp v105, v103 row_shr:4 row_mask:0xf bank_mask:0xa
	s_nop 0
	v_add_f32_e32 v103, v103, v105
	s_nop 1
	v_mov_b32_dpp v105, v103 quad_perm:[2,3,0,1] row_mask:0xf bank_mask:0xf
	v_add_f32_e32 v103, v103, v105
	s_nop 1
	v_add_f32_dpp v103, v103, v103 quad_perm:[1,0,3,2] row_mask:0xf bank_mask:0xf
	v_fmamk_f32 v103, v103, 0x3c000000, v163
	v_cmp_gt_f32_e32 vcc, s86, v103
	v_mul_f32_e32 v105, 0x4b800000, v103
	s_nop 0
	v_cndmask_b32_e32 v103, v103, v105, vcc
	v_rsq_f32_e32 v103, v103
	s_nop 0
	v_mul_f32_e32 v105, 0x45800000, v103
	v_cndmask_b32_e32 v103, v103, v105, vcc
	global_load_ushort v105, v[126:127], off
	v_mul_f32_e32 v126, v242, v103
	global_load_dword v127, v[108:109], off
	v_mul_f32_e32 v124, v124, v103
	s_waitcnt vmcnt(1)
	v_lshlrev_b32_e32 v105, 16, v105
	v_mul_f32_e32 v105, 0xbfb8aa3b, v105
	v_exp_f32_e32 v105, v105
	s_waitcnt vmcnt(0)
	v_mul_f32_e32 v126, v127, v126
	v_add_f32_e32 v105, 1.0, v105
	v_rcp_f32_e32 v105, v105
	s_nop 0
	v_mul_f32_e32 v105, v105, v126
	v_cvt_pk_bf16_f32 v105, v105, s0
	v_lshl_add_u64 v[126:127], v[244:245], 0, v[112:113]
	global_store_short v[122:123], v105, off
	global_load_ushort v105, v[126:127], off
	v_mul_f32_e32 v126, v243, v103
	global_load_dword v127, v[110:111], off offset:128
	v_mul_f32_e32 v103, v125, v103
	s_waitcnt vmcnt(1)
	v_lshlrev_b32_e32 v105, 16, v105
	v_mul_f32_e32 v105, 0xbfb8aa3b, v105
	v_exp_f32_e32 v105, v105
	s_waitcnt vmcnt(0)
	v_mul_f32_e32 v126, v127, v126
	v_add_f32_e32 v105, 1.0, v105
	v_rcp_f32_e32 v105, v105
	s_nop 0
	v_mul_f32_e32 v105, v105, v126
	v_cvt_pk_bf16_f32 v105, v105, s0
	v_lshl_add_u64 v[126:127], v[244:245], 0, v[118:119]
	global_store_short v[122:123], v105, off offset:64
	global_load_ushort v105, v[126:127], off
	s_waitcnt vmcnt(0)
	v_lshlrev_b32_e32 v105, 16, v105
	global_load_dword v126, v[110:111], off offset:256
	v_mul_f32_e32 v105, 0xbfb8aa3b, v105
	v_exp_f32_e32 v105, v105
	s_waitcnt vmcnt(0)
	v_mul_f32_e32 v124, v126, v124
	v_add_f32_e32 v105, 1.0, v105
	v_rcp_f32_e32 v105, v105
	v_lshl_add_u64 v[126:127], v[244:245], 0, v[120:121]
	v_mul_f32_e32 v105, v124, v105
	v_cvt_pk_bf16_f32 v105, v105, s0
	global_store_short v[122:123], v105, off offset:128
	global_load_ushort v105, v[126:127], off
	s_waitcnt vmcnt(0)
	v_lshlrev_b32_e32 v105, 16, v105
	global_load_dword v124, v[110:111], off offset:384
	v_mul_f32_e32 v105, 0xbfb8aa3b, v105
	v_exp_f32_e32 v105, v105
	s_waitcnt vmcnt(0)
	v_mul_f32_e32 v103, v124, v103
	v_add_f32_e32 v105, 1.0, v105
	v_rcp_f32_e32 v105, v105
	s_nop 0
	v_mul_f32_e32 v103, v103, v105
	v_cvt_pk_bf16_f32 v103, v103, s0
	global_store_short v[122:123], v103, off offset:192
	ds_read_b32 v103, v238 offset:32
	ds_read_b32 v105, v239 offset:32
	v_add_u32_e32 v126, 8, v100
	v_ashrrev_i32_e32 v127, 31, v126
	v_mov_b32_e32 v244, v4
	s_waitcnt lgkmcnt(1)
	v_max_f32_e64 v103, |v103|, |v103|
	s_waitcnt lgkmcnt(0)
	v_max_f32_e32 v105, v105, v105
	v_max_f32_e32 v103, v103, v105
	v_div_scale_f32 v105, s[0:1], v103, v103, 1.0
	v_rcp_f32_e32 v122, v105
	v_mov_b32_e32 v245, v20
	v_fma_f32 v123, -v105, v122, 1.0
	v_fmac_f32_e32 v122, v123, v122
	v_div_scale_f32 v123, vcc, 1.0, v103, 1.0
	v_mul_f32_e32 v124, v123, v122
	v_fma_f32 v125, -v105, v124, v123
	v_fmac_f32_e32 v124, v125, v122
	v_fma_f32 v105, -v105, v124, v123
	v_div_fmas_f32 v105, v105, v122, v124
	v_lshlrev_b64 v[124:125], 11, v[126:127]
	v_lshl_add_u64 v[124:125], v[98:99], 0, v[124:125]
	global_load_dword v242, v[124:125], off
	global_load_dword v243, v[124:125], off offset:128
	global_load_dword v246, v[124:125], off offset:256
	global_load_dword v247, v[124:125], off offset:384
	v_div_fixup_f32 v122, v105, v103, 1.0
	v_mov_b32_e32 v124, v36
	v_mov_b32_e32 v125, v52
	s_waitcnt vmcnt(2)
	v_pk_fma_f32 v[242:243], v[244:245], v[122:123], v[242:243] op_sel_hi:[1,0,1]
	v_pk_mul_f32 v[244:245], v[242:243], v[242:243]
	s_waitcnt vmcnt(0)
	v_pk_fma_f32 v[124:125], v[124:125], v[122:123], v[246:247] op_sel_hi:[1,0,1]
	v_add_f32_e32 v103, v244, v245
	v_pk_mul_f32 v[122:123], v[124:125], v[124:125]
	v_add_f32_e32 v103, v103, v122
	v_add_f32_e32 v103, v103, v123
	v_mov_b32_e32 v105, v103
	v_mov_b32_e32 v255, v103
	s_nop 1
	v_permlane16_swap_b32_e32 v105, v255
	s_nop 1
	v_mov_b32_dpp v105, v255 quad_perm:[0,1,2,3] row_mask:0x5 bank_mask:0xf
	v_mad_i64_i32 v[122:123], s[0:1], v126, s74, v[106:107]
	v_lshl_add_u64 v[244:245], v[122:123], 0, s[96:97]
	v_lshlrev_b64 v[122:123], 10, v[126:127]
	v_add_f32_e32 v103, v103, v105
	s_nop 1
	v_mov_b32_dpp v105, v103 row_ror:8 row_mask:0xf bank_mask:0xf
	v_lshl_add_u64 v[126:127], v[244:245], 0, v[96:97]
	v_lshl_add_u64 v[122:123], s[66:67], 0, v[122:123]
	v_lshl_add_u64 v[122:123], v[122:123], 0, v[96:97]
	v_add_f32_e32 v103, v103, v105
	s_nop 1
	v_mov_b32_dpp v105, v103 row_shl:4 row_mask:0xf bank_mask:0x5
	v_mov_b32_dpp v105, v103 row_shr:4 row_mask:0xf bank_mask:0xa
	s_nop 0
	v_add_f32_e32 v103, v103, v105
	s_nop 1
	v_mov_b32_dpp v105, v103 quad_perm:[2,3,0,1] row_mask:0xf bank_mask:0xf
	v_add_f32_e32 v103, v103, v105
	s_nop 1
	v_add_f32_dpp v103, v103, v103 quad_perm:[1,0,3,2] row_mask:0xf bank_mask:0xf
	v_fmamk_f32 v103, v103, 0x3c000000, v163
	v_cmp_gt_f32_e32 vcc, s86, v103
	v_mul_f32_e32 v105, 0x4b800000, v103
	s_nop 0
	v_cndmask_b32_e32 v103, v103, v105, vcc
	v_rsq_f32_e32 v103, v103
	s_nop 0
	v_mul_f32_e32 v105, 0x45800000, v103
	v_cndmask_b32_e32 v103, v103, v105, vcc
	global_load_ushort v105, v[126:127], off
	v_mul_f32_e32 v126, v242, v103
	global_load_dword v127, v[108:109], off
	v_mul_f32_e32 v124, v124, v103
	s_waitcnt vmcnt(1)
	v_lshlrev_b32_e32 v105, 16, v105
	v_mul_f32_e32 v105, 0xbfb8aa3b, v105
	v_exp_f32_e32 v105, v105
	s_waitcnt vmcnt(0)
	v_mul_f32_e32 v126, v127, v126
	v_add_f32_e32 v105, 1.0, v105
	v_rcp_f32_e32 v105, v105
	s_nop 0
	v_mul_f32_e32 v105, v105, v126
	v_cvt_pk_bf16_f32 v105, v105, s0
	v_lshl_add_u64 v[126:127], v[244:245], 0, v[112:113]
	global_store_short v[122:123], v105, off
	global_load_ushort v105, v[126:127], off
	v_mul_f32_e32 v126, v243, v103
	global_load_dword v127, v[110:111], off offset:128
	v_mul_f32_e32 v103, v125, v103
	s_waitcnt vmcnt(1)
	v_lshlrev_b32_e32 v105, 16, v105
	v_mul_f32_e32 v105, 0xbfb8aa3b, v105
	v_exp_f32_e32 v105, v105
	s_waitcnt vmcnt(0)
	v_mul_f32_e32 v126, v127, v126
	v_add_f32_e32 v105, 1.0, v105
	v_rcp_f32_e32 v105, v105
	s_nop 0
	v_mul_f32_e32 v105, v105, v126
	v_cvt_pk_bf16_f32 v105, v105, s0
	v_lshl_add_u64 v[126:127], v[244:245], 0, v[118:119]
	global_store_short v[122:123], v105, off offset:64
	global_load_ushort v105, v[126:127], off
	s_waitcnt vmcnt(0)
	v_lshlrev_b32_e32 v105, 16, v105
	global_load_dword v126, v[110:111], off offset:256
	v_mul_f32_e32 v105, 0xbfb8aa3b, v105
	v_exp_f32_e32 v105, v105
	s_waitcnt vmcnt(0)
	v_mul_f32_e32 v124, v126, v124
	v_add_f32_e32 v105, 1.0, v105
	v_rcp_f32_e32 v105, v105
	v_lshl_add_u64 v[126:127], v[244:245], 0, v[120:121]
	v_mul_f32_e32 v105, v124, v105
	v_cvt_pk_bf16_f32 v105, v105, s0
	global_store_short v[122:123], v105, off offset:128
	global_load_ushort v105, v[126:127], off
	s_waitcnt vmcnt(0)
	v_lshlrev_b32_e32 v105, 16, v105
	global_load_dword v124, v[110:111], off offset:384
	v_mul_f32_e32 v105, 0xbfb8aa3b, v105
	v_exp_f32_e32 v105, v105
	s_waitcnt vmcnt(0)
	v_mul_f32_e32 v103, v124, v103
	v_add_f32_e32 v105, 1.0, v105
	v_rcp_f32_e32 v105, v105
	s_nop 0
	v_mul_f32_e32 v103, v103, v105
	v_cvt_pk_bf16_f32 v103, v103, s0
	global_store_short v[122:123], v103, off offset:192
	ds_read_b32 v103, v238 offset:36
	ds_read_b32 v105, v239 offset:36
	v_add_u32_e32 v126, 9, v100
	v_ashrrev_i32_e32 v127, 31, v126
	v_mov_b32_e32 v244, v5
	s_waitcnt lgkmcnt(1)
	v_max_f32_e64 v103, |v103|, |v103|
	s_waitcnt lgkmcnt(0)
	v_max_f32_e32 v105, v105, v105
	v_max_f32_e32 v103, v103, v105
	v_div_scale_f32 v105, s[0:1], v103, v103, 1.0
	v_rcp_f32_e32 v122, v105
	v_mov_b32_e32 v245, v21
	v_fma_f32 v123, -v105, v122, 1.0
	v_fmac_f32_e32 v122, v123, v122
	v_div_scale_f32 v123, vcc, 1.0, v103, 1.0
	v_mul_f32_e32 v124, v123, v122
	v_fma_f32 v125, -v105, v124, v123
	v_fmac_f32_e32 v124, v125, v122
	v_fma_f32 v105, -v105, v124, v123
	v_div_fmas_f32 v105, v105, v122, v124
	v_lshlrev_b64 v[124:125], 11, v[126:127]
	v_lshl_add_u64 v[124:125], v[98:99], 0, v[124:125]
	global_load_dword v242, v[124:125], off
	global_load_dword v243, v[124:125], off offset:128
	global_load_dword v246, v[124:125], off offset:256
	global_load_dword v247, v[124:125], off offset:384
	v_div_fixup_f32 v122, v105, v103, 1.0
	v_mov_b32_e32 v124, v37
	v_mov_b32_e32 v125, v53
	s_waitcnt vmcnt(2)
	v_pk_fma_f32 v[242:243], v[244:245], v[122:123], v[242:243] op_sel_hi:[1,0,1]
	v_pk_mul_f32 v[244:245], v[242:243], v[242:243]
	s_waitcnt vmcnt(0)
	v_pk_fma_f32 v[124:125], v[124:125], v[122:123], v[246:247] op_sel_hi:[1,0,1]
	v_add_f32_e32 v103, v244, v245
	v_pk_mul_f32 v[122:123], v[124:125], v[124:125]
	v_add_f32_e32 v103, v103, v122
	v_add_f32_e32 v103, v103, v123
	v_mov_b32_e32 v105, v103
	v_mov_b32_e32 v255, v103
	s_nop 1
	v_permlane16_swap_b32_e32 v105, v255
	s_nop 1
	v_mov_b32_dpp v105, v255 quad_perm:[0,1,2,3] row_mask:0x5 bank_mask:0xf
	v_mad_i64_i32 v[122:123], s[0:1], v126, s74, v[106:107]
	v_lshl_add_u64 v[244:245], v[122:123], 0, s[96:97]
	v_lshlrev_b64 v[122:123], 10, v[126:127]
	v_add_f32_e32 v103, v103, v105
	s_nop 1
	v_mov_b32_dpp v105, v103 row_ror:8 row_mask:0xf bank_mask:0xf
	v_lshl_add_u64 v[126:127], v[244:245], 0, v[96:97]
	v_lshl_add_u64 v[122:123], s[66:67], 0, v[122:123]
	v_lshl_add_u64 v[122:123], v[122:123], 0, v[96:97]
	v_add_f32_e32 v103, v103, v105
	s_nop 1
	v_mov_b32_dpp v105, v103 row_shl:4 row_mask:0xf bank_mask:0x5
	v_mov_b32_dpp v105, v103 row_shr:4 row_mask:0xf bank_mask:0xa
	s_nop 0
	v_add_f32_e32 v103, v103, v105
	s_nop 1
	v_mov_b32_dpp v105, v103 quad_perm:[2,3,0,1] row_mask:0xf bank_mask:0xf
	v_add_f32_e32 v103, v103, v105
	s_nop 1
	v_add_f32_dpp v103, v103, v103 quad_perm:[1,0,3,2] row_mask:0xf bank_mask:0xf
	v_fmamk_f32 v103, v103, 0x3c000000, v163
	v_cmp_gt_f32_e32 vcc, s86, v103
	v_mul_f32_e32 v105, 0x4b800000, v103
	s_nop 0
	v_cndmask_b32_e32 v103, v103, v105, vcc
	v_rsq_f32_e32 v103, v103
	s_nop 0
	v_mul_f32_e32 v105, 0x45800000, v103
	v_cndmask_b32_e32 v103, v103, v105, vcc
	global_load_ushort v105, v[126:127], off
	v_mul_f32_e32 v126, v242, v103
	global_load_dword v127, v[108:109], off
	v_mul_f32_e32 v124, v124, v103
	s_waitcnt vmcnt(1)
	v_lshlrev_b32_e32 v105, 16, v105
	v_mul_f32_e32 v105, 0xbfb8aa3b, v105
	v_exp_f32_e32 v105, v105
	s_waitcnt vmcnt(0)
	v_mul_f32_e32 v126, v127, v126
	v_add_f32_e32 v105, 1.0, v105
	v_rcp_f32_e32 v105, v105
	s_nop 0
	v_mul_f32_e32 v105, v105, v126
	v_cvt_pk_bf16_f32 v105, v105, s0
	v_lshl_add_u64 v[126:127], v[244:245], 0, v[112:113]
	global_store_short v[122:123], v105, off
	global_load_ushort v105, v[126:127], off
	v_mul_f32_e32 v126, v243, v103
	global_load_dword v127, v[110:111], off offset:128
	v_mul_f32_e32 v103, v125, v103
	s_waitcnt vmcnt(1)
	v_lshlrev_b32_e32 v105, 16, v105
	v_mul_f32_e32 v105, 0xbfb8aa3b, v105
	v_exp_f32_e32 v105, v105
	s_waitcnt vmcnt(0)
	v_mul_f32_e32 v126, v127, v126
	v_add_f32_e32 v105, 1.0, v105
	v_rcp_f32_e32 v105, v105
	s_nop 0
	v_mul_f32_e32 v105, v105, v126
	v_cvt_pk_bf16_f32 v105, v105, s0
	v_lshl_add_u64 v[126:127], v[244:245], 0, v[118:119]
	global_store_short v[122:123], v105, off offset:64
	global_load_ushort v105, v[126:127], off
	s_waitcnt vmcnt(0)
	v_lshlrev_b32_e32 v105, 16, v105
	global_load_dword v126, v[110:111], off offset:256
	v_mul_f32_e32 v105, 0xbfb8aa3b, v105
	v_exp_f32_e32 v105, v105
	s_waitcnt vmcnt(0)
	v_mul_f32_e32 v124, v126, v124
	v_add_f32_e32 v105, 1.0, v105
	v_rcp_f32_e32 v105, v105
	v_lshl_add_u64 v[126:127], v[244:245], 0, v[120:121]
	v_mul_f32_e32 v105, v124, v105
	v_cvt_pk_bf16_f32 v105, v105, s0
	global_store_short v[122:123], v105, off offset:128
	global_load_ushort v105, v[126:127], off
	s_waitcnt vmcnt(0)
	v_lshlrev_b32_e32 v105, 16, v105
	global_load_dword v124, v[110:111], off offset:384
	v_mul_f32_e32 v105, 0xbfb8aa3b, v105
	v_exp_f32_e32 v105, v105
	s_waitcnt vmcnt(0)
	v_mul_f32_e32 v103, v124, v103
	v_add_f32_e32 v105, 1.0, v105
	v_rcp_f32_e32 v105, v105
	s_nop 0
	v_mul_f32_e32 v103, v103, v105
	v_cvt_pk_bf16_f32 v103, v103, s0
	global_store_short v[122:123], v103, off offset:192
	ds_read_b32 v103, v238 offset:40
	ds_read_b32 v105, v239 offset:40
	v_add_u32_e32 v126, 10, v100
	v_ashrrev_i32_e32 v127, 31, v126
	v_mov_b32_e32 v244, v6
	s_waitcnt lgkmcnt(1)
	v_max_f32_e64 v103, |v103|, |v103|
	s_waitcnt lgkmcnt(0)
	v_max_f32_e32 v105, v105, v105
	v_max_f32_e32 v103, v103, v105
	v_div_scale_f32 v105, s[0:1], v103, v103, 1.0
	v_rcp_f32_e32 v122, v105
	v_mov_b32_e32 v245, v22
	v_fma_f32 v123, -v105, v122, 1.0
	v_fmac_f32_e32 v122, v123, v122
	v_div_scale_f32 v123, vcc, 1.0, v103, 1.0
	v_mul_f32_e32 v124, v123, v122
	v_fma_f32 v125, -v105, v124, v123
	v_fmac_f32_e32 v124, v125, v122
	v_fma_f32 v105, -v105, v124, v123
	v_div_fmas_f32 v105, v105, v122, v124
	v_lshlrev_b64 v[124:125], 11, v[126:127]
	v_lshl_add_u64 v[124:125], v[98:99], 0, v[124:125]
	global_load_dword v242, v[124:125], off
	global_load_dword v243, v[124:125], off offset:128
	global_load_dword v246, v[124:125], off offset:256
	global_load_dword v247, v[124:125], off offset:384
	v_div_fixup_f32 v122, v105, v103, 1.0
	v_mov_b32_e32 v124, v38
	v_mov_b32_e32 v125, v54
	s_waitcnt vmcnt(2)
	v_pk_fma_f32 v[242:243], v[244:245], v[122:123], v[242:243] op_sel_hi:[1,0,1]
	v_pk_mul_f32 v[244:245], v[242:243], v[242:243]
	s_waitcnt vmcnt(0)
	v_pk_fma_f32 v[124:125], v[124:125], v[122:123], v[246:247] op_sel_hi:[1,0,1]
	v_add_f32_e32 v103, v244, v245
	v_pk_mul_f32 v[122:123], v[124:125], v[124:125]
	v_add_f32_e32 v103, v103, v122
	v_add_f32_e32 v103, v103, v123
	v_mov_b32_e32 v105, v103
	v_mov_b32_e32 v255, v103
	s_nop 1
	v_permlane16_swap_b32_e32 v105, v255
	s_nop 1
	v_mov_b32_dpp v105, v255 quad_perm:[0,1,2,3] row_mask:0x5 bank_mask:0xf
	v_mad_i64_i32 v[122:123], s[0:1], v126, s74, v[106:107]
	v_lshl_add_u64 v[244:245], v[122:123], 0, s[96:97]
	v_lshlrev_b64 v[122:123], 10, v[126:127]
	v_add_f32_e32 v103, v103, v105
	s_nop 1
	v_mov_b32_dpp v105, v103 row_ror:8 row_mask:0xf bank_mask:0xf
	v_lshl_add_u64 v[126:127], v[244:245], 0, v[96:97]
	v_lshl_add_u64 v[122:123], s[66:67], 0, v[122:123]
	v_lshl_add_u64 v[122:123], v[122:123], 0, v[96:97]
	v_add_f32_e32 v103, v103, v105
	s_nop 1
	v_mov_b32_dpp v105, v103 row_shl:4 row_mask:0xf bank_mask:0x5
	v_mov_b32_dpp v105, v103 row_shr:4 row_mask:0xf bank_mask:0xa
	s_nop 0
	v_add_f32_e32 v103, v103, v105
	s_nop 1
	v_mov_b32_dpp v105, v103 quad_perm:[2,3,0,1] row_mask:0xf bank_mask:0xf
	v_add_f32_e32 v103, v103, v105
	s_nop 1
	v_add_f32_dpp v103, v103, v103 quad_perm:[1,0,3,2] row_mask:0xf bank_mask:0xf
	v_fmamk_f32 v103, v103, 0x3c000000, v163
	v_cmp_gt_f32_e32 vcc, s86, v103
	v_mul_f32_e32 v105, 0x4b800000, v103
	s_nop 0
	v_cndmask_b32_e32 v103, v103, v105, vcc
	v_rsq_f32_e32 v103, v103
	s_nop 0
	v_mul_f32_e32 v105, 0x45800000, v103
	v_cndmask_b32_e32 v103, v103, v105, vcc
	global_load_ushort v105, v[126:127], off
	v_mul_f32_e32 v126, v242, v103
	global_load_dword v127, v[108:109], off
	v_mul_f32_e32 v124, v124, v103
	s_waitcnt vmcnt(1)
	v_lshlrev_b32_e32 v105, 16, v105
	v_mul_f32_e32 v105, 0xbfb8aa3b, v105
	v_exp_f32_e32 v105, v105
	s_waitcnt vmcnt(0)
	v_mul_f32_e32 v126, v127, v126
	v_add_f32_e32 v105, 1.0, v105
	v_rcp_f32_e32 v105, v105
	s_nop 0
	v_mul_f32_e32 v105, v105, v126
	v_cvt_pk_bf16_f32 v105, v105, s0
	v_lshl_add_u64 v[126:127], v[244:245], 0, v[112:113]
	global_store_short v[122:123], v105, off
	global_load_ushort v105, v[126:127], off
	v_mul_f32_e32 v126, v243, v103
	global_load_dword v127, v[110:111], off offset:128
	v_mul_f32_e32 v103, v125, v103
	s_waitcnt vmcnt(1)
	v_lshlrev_b32_e32 v105, 16, v105
	v_mul_f32_e32 v105, 0xbfb8aa3b, v105
	v_exp_f32_e32 v105, v105
	s_waitcnt vmcnt(0)
	v_mul_f32_e32 v126, v127, v126
	v_add_f32_e32 v105, 1.0, v105
	v_rcp_f32_e32 v105, v105
	s_nop 0
	v_mul_f32_e32 v105, v105, v126
	v_cvt_pk_bf16_f32 v105, v105, s0
	v_lshl_add_u64 v[126:127], v[244:245], 0, v[118:119]
	global_store_short v[122:123], v105, off offset:64
	global_load_ushort v105, v[126:127], off
	s_waitcnt vmcnt(0)
	v_lshlrev_b32_e32 v105, 16, v105
	global_load_dword v126, v[110:111], off offset:256
	v_mul_f32_e32 v105, 0xbfb8aa3b, v105
	v_exp_f32_e32 v105, v105
	s_waitcnt vmcnt(0)
	v_mul_f32_e32 v124, v126, v124
	v_add_f32_e32 v105, 1.0, v105
	v_rcp_f32_e32 v105, v105
	v_lshl_add_u64 v[126:127], v[244:245], 0, v[120:121]
	v_mul_f32_e32 v105, v124, v105
	v_cvt_pk_bf16_f32 v105, v105, s0
	global_store_short v[122:123], v105, off offset:128
	global_load_ushort v105, v[126:127], off
	s_waitcnt vmcnt(0)
	v_lshlrev_b32_e32 v105, 16, v105
	global_load_dword v124, v[110:111], off offset:384
	v_mul_f32_e32 v105, 0xbfb8aa3b, v105
	v_exp_f32_e32 v105, v105
	s_waitcnt vmcnt(0)
	v_mul_f32_e32 v103, v124, v103
	v_add_f32_e32 v105, 1.0, v105
	v_rcp_f32_e32 v105, v105
	s_nop 0
	v_mul_f32_e32 v103, v103, v105
	v_cvt_pk_bf16_f32 v103, v103, s0
	global_store_short v[122:123], v103, off offset:192
	ds_read_b32 v103, v238 offset:44
	ds_read_b32 v105, v239 offset:44
	v_add_u32_e32 v126, 11, v100
	v_ashrrev_i32_e32 v127, 31, v126
	v_mov_b32_e32 v244, v7
	s_waitcnt lgkmcnt(1)
	v_max_f32_e64 v103, |v103|, |v103|
	s_waitcnt lgkmcnt(0)
	v_max_f32_e32 v105, v105, v105
	v_max_f32_e32 v103, v103, v105
	v_div_scale_f32 v105, s[0:1], v103, v103, 1.0
	v_rcp_f32_e32 v122, v105
	v_mov_b32_e32 v245, v23
	v_fma_f32 v123, -v105, v122, 1.0
	v_fmac_f32_e32 v122, v123, v122
	v_div_scale_f32 v123, vcc, 1.0, v103, 1.0
	v_mul_f32_e32 v124, v123, v122
	v_fma_f32 v125, -v105, v124, v123
	v_fmac_f32_e32 v124, v125, v122
	v_fma_f32 v105, -v105, v124, v123
	v_div_fmas_f32 v105, v105, v122, v124
	v_lshlrev_b64 v[124:125], 11, v[126:127]
	v_lshl_add_u64 v[124:125], v[98:99], 0, v[124:125]
	global_load_dword v242, v[124:125], off
	global_load_dword v243, v[124:125], off offset:128
	global_load_dword v246, v[124:125], off offset:256
	global_load_dword v247, v[124:125], off offset:384
	v_div_fixup_f32 v122, v105, v103, 1.0
	v_mov_b32_e32 v124, v39
	v_mov_b32_e32 v125, v55
	s_waitcnt vmcnt(2)
	v_pk_fma_f32 v[242:243], v[244:245], v[122:123], v[242:243] op_sel_hi:[1,0,1]
	v_pk_mul_f32 v[244:245], v[242:243], v[242:243]
	s_waitcnt vmcnt(0)
	v_pk_fma_f32 v[124:125], v[124:125], v[122:123], v[246:247] op_sel_hi:[1,0,1]
	v_add_f32_e32 v103, v244, v245
	v_pk_mul_f32 v[122:123], v[124:125], v[124:125]
	v_add_f32_e32 v103, v103, v122
	v_add_f32_e32 v103, v103, v123
	v_mov_b32_e32 v105, v103
	v_mov_b32_e32 v255, v103
	s_nop 1
	v_permlane16_swap_b32_e32 v105, v255
	s_nop 1
	v_mov_b32_dpp v105, v255 quad_perm:[0,1,2,3] row_mask:0x5 bank_mask:0xf
	v_mad_i64_i32 v[122:123], s[0:1], v126, s74, v[106:107]
	v_lshl_add_u64 v[244:245], v[122:123], 0, s[96:97]
	v_lshlrev_b64 v[122:123], 10, v[126:127]
	v_add_f32_e32 v103, v103, v105
	s_nop 1
	v_mov_b32_dpp v105, v103 row_ror:8 row_mask:0xf bank_mask:0xf
	v_lshl_add_u64 v[126:127], v[244:245], 0, v[96:97]
	v_lshl_add_u64 v[122:123], s[66:67], 0, v[122:123]
	v_lshl_add_u64 v[122:123], v[122:123], 0, v[96:97]
	v_add_f32_e32 v103, v103, v105
	s_nop 1
	v_mov_b32_dpp v105, v103 row_shl:4 row_mask:0xf bank_mask:0x5
	v_mov_b32_dpp v105, v103 row_shr:4 row_mask:0xf bank_mask:0xa
	s_nop 0
	v_add_f32_e32 v103, v103, v105
	s_nop 1
	v_mov_b32_dpp v105, v103 quad_perm:[2,3,0,1] row_mask:0xf bank_mask:0xf
	v_add_f32_e32 v103, v103, v105
	s_nop 1
	v_add_f32_dpp v103, v103, v103 quad_perm:[1,0,3,2] row_mask:0xf bank_mask:0xf
	v_fmamk_f32 v103, v103, 0x3c000000, v163
	v_cmp_gt_f32_e32 vcc, s86, v103
	v_mul_f32_e32 v105, 0x4b800000, v103
	s_nop 0
	v_cndmask_b32_e32 v103, v103, v105, vcc
	v_rsq_f32_e32 v103, v103
	s_nop 0
	v_mul_f32_e32 v105, 0x45800000, v103
	v_cndmask_b32_e32 v103, v103, v105, vcc
	global_load_ushort v105, v[126:127], off
	v_mul_f32_e32 v126, v242, v103
	global_load_dword v127, v[108:109], off
	v_mul_f32_e32 v124, v124, v103
	s_waitcnt vmcnt(1)
	v_lshlrev_b32_e32 v105, 16, v105
	v_mul_f32_e32 v105, 0xbfb8aa3b, v105
	v_exp_f32_e32 v105, v105
	s_waitcnt vmcnt(0)
	v_mul_f32_e32 v126, v127, v126
	v_add_f32_e32 v105, 1.0, v105
	v_rcp_f32_e32 v105, v105
	s_nop 0
	v_mul_f32_e32 v105, v105, v126
	v_cvt_pk_bf16_f32 v105, v105, s0
	v_lshl_add_u64 v[126:127], v[244:245], 0, v[112:113]
	global_store_short v[122:123], v105, off
	global_load_ushort v105, v[126:127], off
	v_mul_f32_e32 v126, v243, v103
	global_load_dword v127, v[110:111], off offset:128
	v_mul_f32_e32 v103, v125, v103
	s_waitcnt vmcnt(1)
	v_lshlrev_b32_e32 v105, 16, v105
	v_mul_f32_e32 v105, 0xbfb8aa3b, v105
	v_exp_f32_e32 v105, v105
	s_waitcnt vmcnt(0)
	v_mul_f32_e32 v126, v127, v126
	v_add_f32_e32 v105, 1.0, v105
	v_rcp_f32_e32 v105, v105
	s_nop 0
	v_mul_f32_e32 v105, v105, v126
	v_cvt_pk_bf16_f32 v105, v105, s0
	v_lshl_add_u64 v[126:127], v[244:245], 0, v[118:119]
	global_store_short v[122:123], v105, off offset:64
	global_load_ushort v105, v[126:127], off
	s_waitcnt vmcnt(0)
	v_lshlrev_b32_e32 v105, 16, v105
	global_load_dword v126, v[110:111], off offset:256
	v_mul_f32_e32 v105, 0xbfb8aa3b, v105
	v_exp_f32_e32 v105, v105
	s_waitcnt vmcnt(0)
	v_mul_f32_e32 v124, v126, v124
	v_add_f32_e32 v105, 1.0, v105
	v_rcp_f32_e32 v105, v105
	v_lshl_add_u64 v[126:127], v[244:245], 0, v[120:121]
	v_mul_f32_e32 v105, v124, v105
	v_cvt_pk_bf16_f32 v105, v105, s0
	global_store_short v[122:123], v105, off offset:128
	global_load_ushort v105, v[126:127], off
	s_waitcnt vmcnt(0)
	v_lshlrev_b32_e32 v105, 16, v105
	global_load_dword v124, v[110:111], off offset:384
	v_mul_f32_e32 v105, 0xbfb8aa3b, v105
	v_exp_f32_e32 v105, v105
	s_waitcnt vmcnt(0)
	v_mul_f32_e32 v103, v124, v103
	v_add_f32_e32 v105, 1.0, v105
	v_rcp_f32_e32 v105, v105
	s_nop 0
	v_mul_f32_e32 v103, v103, v105
	v_cvt_pk_bf16_f32 v103, v103, s0
	global_store_short v[122:123], v103, off offset:192
	ds_read_b32 v103, v238 offset:64
	ds_read_b32 v105, v239 offset:64
	v_add_u32_e32 v126, 16, v100
	v_ashrrev_i32_e32 v127, 31, v126
	v_mov_b32_e32 v244, v8
	s_waitcnt lgkmcnt(1)
	v_max_f32_e64 v103, |v103|, |v103|
	s_waitcnt lgkmcnt(0)
	v_max_f32_e32 v105, v105, v105
	v_max_f32_e32 v103, v103, v105
	v_div_scale_f32 v105, s[0:1], v103, v103, 1.0
	v_rcp_f32_e32 v122, v105
	v_mov_b32_e32 v245, v24
	v_fma_f32 v123, -v105, v122, 1.0
	v_fmac_f32_e32 v122, v123, v122
	v_div_scale_f32 v123, vcc, 1.0, v103, 1.0
	v_mul_f32_e32 v124, v123, v122
	v_fma_f32 v125, -v105, v124, v123
	v_fmac_f32_e32 v124, v125, v122
	v_fma_f32 v105, -v105, v124, v123
	v_div_fmas_f32 v105, v105, v122, v124
	v_lshlrev_b64 v[124:125], 11, v[126:127]
	v_lshl_add_u64 v[124:125], v[98:99], 0, v[124:125]
	global_load_dword v242, v[124:125], off
	global_load_dword v243, v[124:125], off offset:128
	global_load_dword v246, v[124:125], off offset:256
	global_load_dword v247, v[124:125], off offset:384
	v_div_fixup_f32 v122, v105, v103, 1.0
	v_mov_b32_e32 v124, v40
	v_mov_b32_e32 v125, v56
	s_waitcnt vmcnt(2)
	v_pk_fma_f32 v[242:243], v[244:245], v[122:123], v[242:243] op_sel_hi:[1,0,1]
	v_pk_mul_f32 v[244:245], v[242:243], v[242:243]
	s_waitcnt vmcnt(0)
	v_pk_fma_f32 v[124:125], v[124:125], v[122:123], v[246:247] op_sel_hi:[1,0,1]
	v_add_f32_e32 v103, v244, v245
	v_pk_mul_f32 v[122:123], v[124:125], v[124:125]
	v_add_f32_e32 v103, v103, v122
	v_add_f32_e32 v103, v103, v123
	v_mov_b32_e32 v105, v103
	v_mov_b32_e32 v255, v103
	s_nop 1
	v_permlane16_swap_b32_e32 v105, v255
	s_nop 1
	v_mov_b32_dpp v105, v255 quad_perm:[0,1,2,3] row_mask:0x5 bank_mask:0xf
	v_mad_i64_i32 v[122:123], s[0:1], v126, s74, v[106:107]
	v_lshl_add_u64 v[244:245], v[122:123], 0, s[96:97]
	v_lshlrev_b64 v[122:123], 10, v[126:127]
	v_add_f32_e32 v103, v103, v105
	s_nop 1
	v_mov_b32_dpp v105, v103 row_ror:8 row_mask:0xf bank_mask:0xf
	v_lshl_add_u64 v[126:127], v[244:245], 0, v[96:97]
	v_lshl_add_u64 v[122:123], s[66:67], 0, v[122:123]
	v_lshl_add_u64 v[122:123], v[122:123], 0, v[96:97]
	v_add_f32_e32 v103, v103, v105
	s_nop 1
	v_mov_b32_dpp v105, v103 row_shl:4 row_mask:0xf bank_mask:0x5
	v_mov_b32_dpp v105, v103 row_shr:4 row_mask:0xf bank_mask:0xa
	s_nop 0
	v_add_f32_e32 v103, v103, v105
	s_nop 1
	v_mov_b32_dpp v105, v103 quad_perm:[2,3,0,1] row_mask:0xf bank_mask:0xf
	v_add_f32_e32 v103, v103, v105
	s_nop 1
	v_add_f32_dpp v103, v103, v103 quad_perm:[1,0,3,2] row_mask:0xf bank_mask:0xf
	v_fmamk_f32 v103, v103, 0x3c000000, v163
	v_cmp_gt_f32_e32 vcc, s86, v103
	v_mul_f32_e32 v105, 0x4b800000, v103
	s_nop 0
	v_cndmask_b32_e32 v103, v103, v105, vcc
	v_rsq_f32_e32 v103, v103
	s_nop 0
	v_mul_f32_e32 v105, 0x45800000, v103
	v_cndmask_b32_e32 v103, v103, v105, vcc
	global_load_ushort v105, v[126:127], off
	v_mul_f32_e32 v126, v242, v103
	global_load_dword v127, v[108:109], off
	v_mul_f32_e32 v124, v124, v103
	s_waitcnt vmcnt(1)
	v_lshlrev_b32_e32 v105, 16, v105
	v_mul_f32_e32 v105, 0xbfb8aa3b, v105
	v_exp_f32_e32 v105, v105
	s_waitcnt vmcnt(0)
	v_mul_f32_e32 v126, v127, v126
	v_add_f32_e32 v105, 1.0, v105
	v_rcp_f32_e32 v105, v105
	s_nop 0
	v_mul_f32_e32 v105, v105, v126
	v_cvt_pk_bf16_f32 v105, v105, s0
	v_lshl_add_u64 v[126:127], v[244:245], 0, v[112:113]
	global_store_short v[122:123], v105, off
	global_load_ushort v105, v[126:127], off
	v_mul_f32_e32 v126, v243, v103
	global_load_dword v127, v[110:111], off offset:128
	v_mul_f32_e32 v103, v125, v103
	s_waitcnt vmcnt(1)
	v_lshlrev_b32_e32 v105, 16, v105
	v_mul_f32_e32 v105, 0xbfb8aa3b, v105
	v_exp_f32_e32 v105, v105
	s_waitcnt vmcnt(0)
	v_mul_f32_e32 v126, v127, v126
	v_add_f32_e32 v105, 1.0, v105
	v_rcp_f32_e32 v105, v105
	s_nop 0
	v_mul_f32_e32 v105, v105, v126
	v_cvt_pk_bf16_f32 v105, v105, s0
	v_lshl_add_u64 v[126:127], v[244:245], 0, v[118:119]
	global_store_short v[122:123], v105, off offset:64
	global_load_ushort v105, v[126:127], off
	s_waitcnt vmcnt(0)
	v_lshlrev_b32_e32 v105, 16, v105
	global_load_dword v126, v[110:111], off offset:256
	v_mul_f32_e32 v105, 0xbfb8aa3b, v105
	v_exp_f32_e32 v105, v105
	s_waitcnt vmcnt(0)
	v_mul_f32_e32 v124, v126, v124
	v_add_f32_e32 v105, 1.0, v105
	v_rcp_f32_e32 v105, v105
	v_lshl_add_u64 v[126:127], v[244:245], 0, v[120:121]
	v_mul_f32_e32 v105, v124, v105
	v_cvt_pk_bf16_f32 v105, v105, s0
	global_store_short v[122:123], v105, off offset:128
	global_load_ushort v105, v[126:127], off
	s_waitcnt vmcnt(0)
	v_lshlrev_b32_e32 v105, 16, v105
	global_load_dword v124, v[110:111], off offset:384
	v_mul_f32_e32 v105, 0xbfb8aa3b, v105
	v_exp_f32_e32 v105, v105
	s_waitcnt vmcnt(0)
	v_mul_f32_e32 v103, v124, v103
	v_add_f32_e32 v105, 1.0, v105
	v_rcp_f32_e32 v105, v105
	s_nop 0
	v_mul_f32_e32 v103, v103, v105
	v_cvt_pk_bf16_f32 v103, v103, s0
	global_store_short v[122:123], v103, off offset:192
	ds_read_b32 v103, v238 offset:68
	ds_read_b32 v105, v239 offset:68
	v_add_u32_e32 v126, 17, v100
	v_ashrrev_i32_e32 v127, 31, v126
	v_mov_b32_e32 v244, v9
	s_waitcnt lgkmcnt(1)
	v_max_f32_e64 v103, |v103|, |v103|
	s_waitcnt lgkmcnt(0)
	v_max_f32_e32 v105, v105, v105
	v_max_f32_e32 v103, v103, v105
	v_div_scale_f32 v105, s[0:1], v103, v103, 1.0
	v_rcp_f32_e32 v122, v105
	v_mov_b32_e32 v245, v25
	v_fma_f32 v123, -v105, v122, 1.0
	v_fmac_f32_e32 v122, v123, v122
	v_div_scale_f32 v123, vcc, 1.0, v103, 1.0
	v_mul_f32_e32 v124, v123, v122
	v_fma_f32 v125, -v105, v124, v123
	v_fmac_f32_e32 v124, v125, v122
	v_fma_f32 v105, -v105, v124, v123
	v_div_fmas_f32 v105, v105, v122, v124
	v_lshlrev_b64 v[124:125], 11, v[126:127]
	v_lshl_add_u64 v[124:125], v[98:99], 0, v[124:125]
	global_load_dword v242, v[124:125], off
	global_load_dword v243, v[124:125], off offset:128
	global_load_dword v246, v[124:125], off offset:256
	global_load_dword v247, v[124:125], off offset:384
	v_div_fixup_f32 v122, v105, v103, 1.0
	v_mov_b32_e32 v124, v41
	v_mov_b32_e32 v125, v57
	s_waitcnt vmcnt(2)
	v_pk_fma_f32 v[242:243], v[244:245], v[122:123], v[242:243] op_sel_hi:[1,0,1]
	v_pk_mul_f32 v[244:245], v[242:243], v[242:243]
	s_waitcnt vmcnt(0)
	v_pk_fma_f32 v[124:125], v[124:125], v[122:123], v[246:247] op_sel_hi:[1,0,1]
	v_add_f32_e32 v103, v244, v245
	v_pk_mul_f32 v[122:123], v[124:125], v[124:125]
	v_add_f32_e32 v103, v103, v122
	v_add_f32_e32 v103, v103, v123
	v_mov_b32_e32 v105, v103
	v_mov_b32_e32 v255, v103
	s_nop 1
	v_permlane16_swap_b32_e32 v105, v255
	s_nop 1
	v_mov_b32_dpp v105, v255 quad_perm:[0,1,2,3] row_mask:0x5 bank_mask:0xf
	v_mad_i64_i32 v[122:123], s[0:1], v126, s74, v[106:107]
	v_lshl_add_u64 v[244:245], v[122:123], 0, s[96:97]
	v_lshlrev_b64 v[122:123], 10, v[126:127]
	v_add_f32_e32 v103, v103, v105
	s_nop 1
	v_mov_b32_dpp v105, v103 row_ror:8 row_mask:0xf bank_mask:0xf
	v_lshl_add_u64 v[126:127], v[244:245], 0, v[96:97]
	v_lshl_add_u64 v[122:123], s[66:67], 0, v[122:123]
	v_lshl_add_u64 v[122:123], v[122:123], 0, v[96:97]
	v_add_f32_e32 v103, v103, v105
	s_nop 1
	v_mov_b32_dpp v105, v103 row_shl:4 row_mask:0xf bank_mask:0x5
	v_mov_b32_dpp v105, v103 row_shr:4 row_mask:0xf bank_mask:0xa
	s_nop 0
	v_add_f32_e32 v103, v103, v105
	s_nop 1
	v_mov_b32_dpp v105, v103 quad_perm:[2,3,0,1] row_mask:0xf bank_mask:0xf
	v_add_f32_e32 v103, v103, v105
	s_nop 1
	v_add_f32_dpp v103, v103, v103 quad_perm:[1,0,3,2] row_mask:0xf bank_mask:0xf
	v_fmamk_f32 v103, v103, 0x3c000000, v163
	v_cmp_gt_f32_e32 vcc, s86, v103
	v_mul_f32_e32 v105, 0x4b800000, v103
	s_nop 0
	v_cndmask_b32_e32 v103, v103, v105, vcc
	v_rsq_f32_e32 v103, v103
	s_nop 0
	v_mul_f32_e32 v105, 0x45800000, v103
	v_cndmask_b32_e32 v103, v103, v105, vcc
	global_load_ushort v105, v[126:127], off
	v_mul_f32_e32 v126, v242, v103
	global_load_dword v127, v[108:109], off
	v_mul_f32_e32 v124, v124, v103
	s_waitcnt vmcnt(1)
	v_lshlrev_b32_e32 v105, 16, v105
	v_mul_f32_e32 v105, 0xbfb8aa3b, v105
	v_exp_f32_e32 v105, v105
	s_waitcnt vmcnt(0)
	v_mul_f32_e32 v126, v127, v126
	v_add_f32_e32 v105, 1.0, v105
	v_rcp_f32_e32 v105, v105
	s_nop 0
	v_mul_f32_e32 v105, v105, v126
	v_cvt_pk_bf16_f32 v105, v105, s0
	v_lshl_add_u64 v[126:127], v[244:245], 0, v[112:113]
	global_store_short v[122:123], v105, off
	global_load_ushort v105, v[126:127], off
	v_mul_f32_e32 v126, v243, v103
	global_load_dword v127, v[110:111], off offset:128
	v_mul_f32_e32 v103, v125, v103
	s_waitcnt vmcnt(1)
	v_lshlrev_b32_e32 v105, 16, v105
	v_mul_f32_e32 v105, 0xbfb8aa3b, v105
	v_exp_f32_e32 v105, v105
	s_waitcnt vmcnt(0)
	v_mul_f32_e32 v126, v127, v126
	v_add_f32_e32 v105, 1.0, v105
	v_rcp_f32_e32 v105, v105
	s_nop 0
	v_mul_f32_e32 v105, v105, v126
	v_cvt_pk_bf16_f32 v105, v105, s0
	v_lshl_add_u64 v[126:127], v[244:245], 0, v[118:119]
	global_store_short v[122:123], v105, off offset:64
	global_load_ushort v105, v[126:127], off
	s_waitcnt vmcnt(0)
	v_lshlrev_b32_e32 v105, 16, v105
	global_load_dword v126, v[110:111], off offset:256
	v_mul_f32_e32 v105, 0xbfb8aa3b, v105
	v_exp_f32_e32 v105, v105
	s_waitcnt vmcnt(0)
	v_mul_f32_e32 v124, v126, v124
	v_add_f32_e32 v105, 1.0, v105
	v_rcp_f32_e32 v105, v105
	v_lshl_add_u64 v[126:127], v[244:245], 0, v[120:121]
	v_mul_f32_e32 v105, v124, v105
	v_cvt_pk_bf16_f32 v105, v105, s0
	global_store_short v[122:123], v105, off offset:128
	global_load_ushort v105, v[126:127], off
	s_waitcnt vmcnt(0)
	v_lshlrev_b32_e32 v105, 16, v105
	global_load_dword v124, v[110:111], off offset:384
	v_mul_f32_e32 v105, 0xbfb8aa3b, v105
	v_exp_f32_e32 v105, v105
	s_waitcnt vmcnt(0)
	v_mul_f32_e32 v103, v124, v103
	v_add_f32_e32 v105, 1.0, v105
	v_rcp_f32_e32 v105, v105
	s_nop 0
	v_mul_f32_e32 v103, v103, v105
	v_cvt_pk_bf16_f32 v103, v103, s0
	global_store_short v[122:123], v103, off offset:192
	ds_read_b32 v103, v238 offset:72
	ds_read_b32 v105, v239 offset:72
	v_add_u32_e32 v126, 18, v100
	v_ashrrev_i32_e32 v127, 31, v126
	v_mov_b32_e32 v244, v10
	s_waitcnt lgkmcnt(1)
	v_max_f32_e64 v103, |v103|, |v103|
	s_waitcnt lgkmcnt(0)
	v_max_f32_e32 v105, v105, v105
	v_max_f32_e32 v103, v103, v105
	v_div_scale_f32 v105, s[0:1], v103, v103, 1.0
	v_rcp_f32_e32 v122, v105
	v_mov_b32_e32 v245, v26
	v_fma_f32 v123, -v105, v122, 1.0
	v_fmac_f32_e32 v122, v123, v122
	v_div_scale_f32 v123, vcc, 1.0, v103, 1.0
	v_mul_f32_e32 v124, v123, v122
	v_fma_f32 v125, -v105, v124, v123
	v_fmac_f32_e32 v124, v125, v122
	v_fma_f32 v105, -v105, v124, v123
	v_div_fmas_f32 v105, v105, v122, v124
	v_lshlrev_b64 v[124:125], 11, v[126:127]
	v_lshl_add_u64 v[124:125], v[98:99], 0, v[124:125]
	global_load_dword v242, v[124:125], off
	global_load_dword v243, v[124:125], off offset:128
	global_load_dword v246, v[124:125], off offset:256
	global_load_dword v247, v[124:125], off offset:384
	v_div_fixup_f32 v122, v105, v103, 1.0
	v_mov_b32_e32 v124, v42
	v_mov_b32_e32 v125, v58
	s_waitcnt vmcnt(2)
	v_pk_fma_f32 v[242:243], v[244:245], v[122:123], v[242:243] op_sel_hi:[1,0,1]
	v_pk_mul_f32 v[244:245], v[242:243], v[242:243]
	s_waitcnt vmcnt(0)
	v_pk_fma_f32 v[124:125], v[124:125], v[122:123], v[246:247] op_sel_hi:[1,0,1]
	v_add_f32_e32 v103, v244, v245
	v_pk_mul_f32 v[122:123], v[124:125], v[124:125]
	v_add_f32_e32 v103, v103, v122
	v_add_f32_e32 v103, v103, v123
	v_mov_b32_e32 v105, v103
	v_mov_b32_e32 v255, v103
	s_nop 1
	v_permlane16_swap_b32_e32 v105, v255
	s_nop 1
	v_mov_b32_dpp v105, v255 quad_perm:[0,1,2,3] row_mask:0x5 bank_mask:0xf
	v_mad_i64_i32 v[122:123], s[0:1], v126, s74, v[106:107]
	v_lshl_add_u64 v[244:245], v[122:123], 0, s[96:97]
	v_lshlrev_b64 v[122:123], 10, v[126:127]
	v_add_f32_e32 v103, v103, v105
	s_nop 1
	v_mov_b32_dpp v105, v103 row_ror:8 row_mask:0xf bank_mask:0xf
	v_lshl_add_u64 v[126:127], v[244:245], 0, v[96:97]
	v_lshl_add_u64 v[122:123], s[66:67], 0, v[122:123]
	v_lshl_add_u64 v[122:123], v[122:123], 0, v[96:97]
	v_add_f32_e32 v103, v103, v105
	s_nop 1
	v_mov_b32_dpp v105, v103 row_shl:4 row_mask:0xf bank_mask:0x5
	v_mov_b32_dpp v105, v103 row_shr:4 row_mask:0xf bank_mask:0xa
	s_nop 0
	v_add_f32_e32 v103, v103, v105
	s_nop 1
	v_mov_b32_dpp v105, v103 quad_perm:[2,3,0,1] row_mask:0xf bank_mask:0xf
	v_add_f32_e32 v103, v103, v105
	s_nop 1
	v_add_f32_dpp v103, v103, v103 quad_perm:[1,0,3,2] row_mask:0xf bank_mask:0xf
	v_fmamk_f32 v103, v103, 0x3c000000, v163
	v_cmp_gt_f32_e32 vcc, s86, v103
	v_mul_f32_e32 v105, 0x4b800000, v103
	s_nop 0
	v_cndmask_b32_e32 v103, v103, v105, vcc
	v_rsq_f32_e32 v103, v103
	s_nop 0
	v_mul_f32_e32 v105, 0x45800000, v103
	v_cndmask_b32_e32 v103, v103, v105, vcc
	global_load_ushort v105, v[126:127], off
	v_mul_f32_e32 v126, v242, v103
	global_load_dword v127, v[108:109], off
	v_mul_f32_e32 v124, v124, v103
	s_waitcnt vmcnt(1)
	v_lshlrev_b32_e32 v105, 16, v105
	v_mul_f32_e32 v105, 0xbfb8aa3b, v105
	v_exp_f32_e32 v105, v105
	s_waitcnt vmcnt(0)
	v_mul_f32_e32 v126, v127, v126
	v_add_f32_e32 v105, 1.0, v105
	v_rcp_f32_e32 v105, v105
	s_nop 0
	v_mul_f32_e32 v105, v105, v126
	v_cvt_pk_bf16_f32 v105, v105, s0
	v_lshl_add_u64 v[126:127], v[244:245], 0, v[112:113]
	global_store_short v[122:123], v105, off
	global_load_ushort v105, v[126:127], off
	v_mul_f32_e32 v126, v243, v103
	global_load_dword v127, v[110:111], off offset:128
	v_mul_f32_e32 v103, v125, v103
	s_waitcnt vmcnt(1)
	v_lshlrev_b32_e32 v105, 16, v105
	v_mul_f32_e32 v105, 0xbfb8aa3b, v105
	v_exp_f32_e32 v105, v105
	s_waitcnt vmcnt(0)
	v_mul_f32_e32 v126, v127, v126
	v_add_f32_e32 v105, 1.0, v105
	v_rcp_f32_e32 v105, v105
	s_nop 0
	v_mul_f32_e32 v105, v105, v126
	v_cvt_pk_bf16_f32 v105, v105, s0
	v_lshl_add_u64 v[126:127], v[244:245], 0, v[118:119]
	global_store_short v[122:123], v105, off offset:64
	global_load_ushort v105, v[126:127], off
	s_waitcnt vmcnt(0)
	v_lshlrev_b32_e32 v105, 16, v105
	global_load_dword v126, v[110:111], off offset:256
	v_mul_f32_e32 v105, 0xbfb8aa3b, v105
	v_exp_f32_e32 v105, v105
	s_waitcnt vmcnt(0)
	v_mul_f32_e32 v124, v126, v124
	v_add_f32_e32 v105, 1.0, v105
	v_rcp_f32_e32 v105, v105
	v_lshl_add_u64 v[126:127], v[244:245], 0, v[120:121]
	v_mul_f32_e32 v105, v124, v105
	v_cvt_pk_bf16_f32 v105, v105, s0
	global_store_short v[122:123], v105, off offset:128
	global_load_ushort v105, v[126:127], off
	s_waitcnt vmcnt(0)
	v_lshlrev_b32_e32 v105, 16, v105
	global_load_dword v124, v[110:111], off offset:384
	v_mul_f32_e32 v105, 0xbfb8aa3b, v105
	v_exp_f32_e32 v105, v105
	s_waitcnt vmcnt(0)
	v_mul_f32_e32 v103, v124, v103
	v_add_f32_e32 v105, 1.0, v105
	v_rcp_f32_e32 v105, v105
	s_nop 0
	v_mul_f32_e32 v103, v103, v105
	v_cvt_pk_bf16_f32 v103, v103, s0
	global_store_short v[122:123], v103, off offset:192
	ds_read_b32 v103, v238 offset:76
	ds_read_b32 v105, v239 offset:76
	v_add_u32_e32 v126, 19, v100
	v_ashrrev_i32_e32 v127, 31, v126
	v_mov_b32_e32 v244, v11
	s_waitcnt lgkmcnt(1)
	v_max_f32_e64 v103, |v103|, |v103|
	s_waitcnt lgkmcnt(0)
	v_max_f32_e32 v105, v105, v105
	v_max_f32_e32 v103, v103, v105
	v_div_scale_f32 v105, s[0:1], v103, v103, 1.0
	v_rcp_f32_e32 v122, v105
	v_mov_b32_e32 v245, v27
	v_fma_f32 v123, -v105, v122, 1.0
	v_fmac_f32_e32 v122, v123, v122
	v_div_scale_f32 v123, vcc, 1.0, v103, 1.0
	v_mul_f32_e32 v124, v123, v122
	v_fma_f32 v125, -v105, v124, v123
	v_fmac_f32_e32 v124, v125, v122
	v_fma_f32 v105, -v105, v124, v123
	v_div_fmas_f32 v105, v105, v122, v124
	v_lshlrev_b64 v[124:125], 11, v[126:127]
	v_lshl_add_u64 v[124:125], v[98:99], 0, v[124:125]
	global_load_dword v242, v[124:125], off
	global_load_dword v243, v[124:125], off offset:128
	global_load_dword v246, v[124:125], off offset:256
	global_load_dword v247, v[124:125], off offset:384
	v_div_fixup_f32 v122, v105, v103, 1.0
	v_mov_b32_e32 v124, v43
	v_mov_b32_e32 v125, v59
	s_waitcnt vmcnt(2)
	v_pk_fma_f32 v[242:243], v[244:245], v[122:123], v[242:243] op_sel_hi:[1,0,1]
	v_pk_mul_f32 v[244:245], v[242:243], v[242:243]
	s_waitcnt vmcnt(0)
	v_pk_fma_f32 v[124:125], v[124:125], v[122:123], v[246:247] op_sel_hi:[1,0,1]
	v_add_f32_e32 v103, v244, v245
	v_pk_mul_f32 v[122:123], v[124:125], v[124:125]
	v_add_f32_e32 v103, v103, v122
	v_add_f32_e32 v103, v103, v123
	v_mov_b32_e32 v105, v103
	v_mov_b32_e32 v255, v103
	s_nop 1
	v_permlane16_swap_b32_e32 v105, v255
	s_nop 1
	v_mov_b32_dpp v105, v255 quad_perm:[0,1,2,3] row_mask:0x5 bank_mask:0xf
	v_mad_i64_i32 v[122:123], s[0:1], v126, s74, v[106:107]
	v_lshl_add_u64 v[244:245], v[122:123], 0, s[96:97]
	v_lshlrev_b64 v[122:123], 10, v[126:127]
	v_add_f32_e32 v103, v103, v105
	s_nop 1
	v_mov_b32_dpp v105, v103 row_ror:8 row_mask:0xf bank_mask:0xf
	v_lshl_add_u64 v[126:127], v[244:245], 0, v[96:97]
	v_lshl_add_u64 v[122:123], s[66:67], 0, v[122:123]
	v_lshl_add_u64 v[122:123], v[122:123], 0, v[96:97]
	v_add_f32_e32 v103, v103, v105
	s_nop 1
	v_mov_b32_dpp v105, v103 row_shl:4 row_mask:0xf bank_mask:0x5
	v_mov_b32_dpp v105, v103 row_shr:4 row_mask:0xf bank_mask:0xa
	s_nop 0
	v_add_f32_e32 v103, v103, v105
	s_nop 1
	v_mov_b32_dpp v105, v103 quad_perm:[2,3,0,1] row_mask:0xf bank_mask:0xf
	v_add_f32_e32 v103, v103, v105
	s_nop 1
	v_add_f32_dpp v103, v103, v103 quad_perm:[1,0,3,2] row_mask:0xf bank_mask:0xf
	v_fmamk_f32 v103, v103, 0x3c000000, v163
	v_cmp_gt_f32_e32 vcc, s86, v103
	v_mul_f32_e32 v105, 0x4b800000, v103
	s_nop 0
	v_cndmask_b32_e32 v103, v103, v105, vcc
	v_rsq_f32_e32 v103, v103
	s_nop 0
	v_mul_f32_e32 v105, 0x45800000, v103
	v_cndmask_b32_e32 v103, v103, v105, vcc
	global_load_ushort v105, v[126:127], off
	v_mul_f32_e32 v126, v242, v103
	global_load_dword v127, v[108:109], off
	v_mul_f32_e32 v124, v124, v103
	s_waitcnt vmcnt(1)
	v_lshlrev_b32_e32 v105, 16, v105
	v_mul_f32_e32 v105, 0xbfb8aa3b, v105
	v_exp_f32_e32 v105, v105
	s_waitcnt vmcnt(0)
	v_mul_f32_e32 v126, v127, v126
	v_add_f32_e32 v105, 1.0, v105
	v_rcp_f32_e32 v105, v105
	s_nop 0
	v_mul_f32_e32 v105, v105, v126
	v_cvt_pk_bf16_f32 v105, v105, s0
	v_lshl_add_u64 v[126:127], v[244:245], 0, v[112:113]
	global_store_short v[122:123], v105, off
	global_load_ushort v105, v[126:127], off
	v_mul_f32_e32 v126, v243, v103
	global_load_dword v127, v[110:111], off offset:128
	v_mul_f32_e32 v103, v125, v103
	s_waitcnt vmcnt(1)
	v_lshlrev_b32_e32 v105, 16, v105
	v_mul_f32_e32 v105, 0xbfb8aa3b, v105
	v_exp_f32_e32 v105, v105
	s_waitcnt vmcnt(0)
	v_mul_f32_e32 v126, v127, v126
	v_add_f32_e32 v105, 1.0, v105
	v_rcp_f32_e32 v105, v105
	s_nop 0
	v_mul_f32_e32 v105, v105, v126
	v_cvt_pk_bf16_f32 v105, v105, s0
	v_lshl_add_u64 v[126:127], v[244:245], 0, v[118:119]
	global_store_short v[122:123], v105, off offset:64
	global_load_ushort v105, v[126:127], off
	s_waitcnt vmcnt(0)
	v_lshlrev_b32_e32 v105, 16, v105
	global_load_dword v126, v[110:111], off offset:256
	v_mul_f32_e32 v105, 0xbfb8aa3b, v105
	v_exp_f32_e32 v105, v105
	s_waitcnt vmcnt(0)
	v_mul_f32_e32 v124, v126, v124
	v_add_f32_e32 v105, 1.0, v105
	v_rcp_f32_e32 v105, v105
	v_lshl_add_u64 v[126:127], v[244:245], 0, v[120:121]
	v_mul_f32_e32 v105, v124, v105
	v_cvt_pk_bf16_f32 v105, v105, s0
	global_store_short v[122:123], v105, off offset:128
	global_load_ushort v105, v[126:127], off
	s_waitcnt vmcnt(0)
	v_lshlrev_b32_e32 v105, 16, v105
	global_load_dword v124, v[110:111], off offset:384
	v_mul_f32_e32 v105, 0xbfb8aa3b, v105
	v_exp_f32_e32 v105, v105
	s_waitcnt vmcnt(0)
	v_mul_f32_e32 v103, v124, v103
	v_add_f32_e32 v105, 1.0, v105
	v_rcp_f32_e32 v105, v105
	s_nop 0
	v_mul_f32_e32 v103, v103, v105
	v_cvt_pk_bf16_f32 v103, v103, s0
	global_store_short v[122:123], v103, off offset:192
	ds_read_b32 v103, v238 offset:96
	ds_read_b32 v105, v239 offset:96
	v_add_u32_e32 v126, 24, v100
	v_ashrrev_i32_e32 v127, 31, v126
	v_mov_b32_e32 v244, v12
	s_waitcnt lgkmcnt(1)
	v_max_f32_e64 v103, |v103|, |v103|
	s_waitcnt lgkmcnt(0)
	v_max_f32_e32 v105, v105, v105
	v_max_f32_e32 v103, v103, v105
	v_div_scale_f32 v105, s[0:1], v103, v103, 1.0
	v_rcp_f32_e32 v122, v105
	v_mov_b32_e32 v245, v28
	v_fma_f32 v123, -v105, v122, 1.0
	v_fmac_f32_e32 v122, v123, v122
	v_div_scale_f32 v123, vcc, 1.0, v103, 1.0
	v_mul_f32_e32 v124, v123, v122
	v_fma_f32 v125, -v105, v124, v123
	v_fmac_f32_e32 v124, v125, v122
	v_fma_f32 v105, -v105, v124, v123
	v_div_fmas_f32 v105, v105, v122, v124
	v_lshlrev_b64 v[124:125], 11, v[126:127]
	v_lshl_add_u64 v[124:125], v[98:99], 0, v[124:125]
	global_load_dword v242, v[124:125], off
	global_load_dword v243, v[124:125], off offset:128
	global_load_dword v246, v[124:125], off offset:256
	global_load_dword v247, v[124:125], off offset:384
	v_div_fixup_f32 v122, v105, v103, 1.0
	v_mov_b32_e32 v124, v44
	v_mov_b32_e32 v125, v60
	s_waitcnt vmcnt(2)
	v_pk_fma_f32 v[242:243], v[244:245], v[122:123], v[242:243] op_sel_hi:[1,0,1]
	v_pk_mul_f32 v[244:245], v[242:243], v[242:243]
	s_waitcnt vmcnt(0)
	v_pk_fma_f32 v[124:125], v[124:125], v[122:123], v[246:247] op_sel_hi:[1,0,1]
	v_add_f32_e32 v103, v244, v245
	v_pk_mul_f32 v[122:123], v[124:125], v[124:125]
	v_add_f32_e32 v103, v103, v122
	v_add_f32_e32 v103, v103, v123
	v_mov_b32_e32 v105, v103
	v_mov_b32_e32 v255, v103
	s_nop 1
	v_permlane16_swap_b32_e32 v105, v255
	s_nop 1
	v_mov_b32_dpp v105, v255 quad_perm:[0,1,2,3] row_mask:0x5 bank_mask:0xf
	v_mad_i64_i32 v[122:123], s[0:1], v126, s74, v[106:107]
	v_lshl_add_u64 v[244:245], v[122:123], 0, s[96:97]
	v_lshlrev_b64 v[122:123], 10, v[126:127]
	v_add_f32_e32 v103, v103, v105
	s_nop 1
	v_mov_b32_dpp v105, v103 row_ror:8 row_mask:0xf bank_mask:0xf
	v_lshl_add_u64 v[126:127], v[244:245], 0, v[96:97]
	v_lshl_add_u64 v[122:123], s[66:67], 0, v[122:123]
	v_lshl_add_u64 v[122:123], v[122:123], 0, v[96:97]
	v_add_f32_e32 v103, v103, v105
	s_nop 1
	v_mov_b32_dpp v105, v103 row_shl:4 row_mask:0xf bank_mask:0x5
	v_mov_b32_dpp v105, v103 row_shr:4 row_mask:0xf bank_mask:0xa
	s_nop 0
	v_add_f32_e32 v103, v103, v105
	s_nop 1
	v_mov_b32_dpp v105, v103 quad_perm:[2,3,0,1] row_mask:0xf bank_mask:0xf
	v_add_f32_e32 v103, v103, v105
	s_nop 1
	v_add_f32_dpp v103, v103, v103 quad_perm:[1,0,3,2] row_mask:0xf bank_mask:0xf
	v_fmamk_f32 v103, v103, 0x3c000000, v163
	v_cmp_gt_f32_e32 vcc, s86, v103
	v_mul_f32_e32 v105, 0x4b800000, v103
	s_nop 0
	v_cndmask_b32_e32 v103, v103, v105, vcc
	v_rsq_f32_e32 v103, v103
	s_nop 0
	v_mul_f32_e32 v105, 0x45800000, v103
	v_cndmask_b32_e32 v103, v103, v105, vcc
	global_load_ushort v105, v[126:127], off
	v_mul_f32_e32 v126, v242, v103
	global_load_dword v127, v[108:109], off
	v_mul_f32_e32 v124, v124, v103
	s_waitcnt vmcnt(1)
	v_lshlrev_b32_e32 v105, 16, v105
	v_mul_f32_e32 v105, 0xbfb8aa3b, v105
	v_exp_f32_e32 v105, v105
	s_waitcnt vmcnt(0)
	v_mul_f32_e32 v126, v127, v126
	v_add_f32_e32 v105, 1.0, v105
	v_rcp_f32_e32 v105, v105
	s_nop 0
	v_mul_f32_e32 v105, v105, v126
	v_cvt_pk_bf16_f32 v105, v105, s0
	v_lshl_add_u64 v[126:127], v[244:245], 0, v[112:113]
	global_store_short v[122:123], v105, off
	global_load_ushort v105, v[126:127], off
	v_mul_f32_e32 v126, v243, v103
	global_load_dword v127, v[110:111], off offset:128
	v_mul_f32_e32 v103, v125, v103
	s_waitcnt vmcnt(1)
	v_lshlrev_b32_e32 v105, 16, v105
	v_mul_f32_e32 v105, 0xbfb8aa3b, v105
	v_exp_f32_e32 v105, v105
	s_waitcnt vmcnt(0)
	v_mul_f32_e32 v126, v127, v126
	v_add_f32_e32 v105, 1.0, v105
	v_rcp_f32_e32 v105, v105
	s_nop 0
	v_mul_f32_e32 v105, v105, v126
	v_cvt_pk_bf16_f32 v105, v105, s0
	v_lshl_add_u64 v[126:127], v[244:245], 0, v[118:119]
	global_store_short v[122:123], v105, off offset:64
	global_load_ushort v105, v[126:127], off
	s_waitcnt vmcnt(0)
	v_lshlrev_b32_e32 v105, 16, v105
	global_load_dword v126, v[110:111], off offset:256
	v_mul_f32_e32 v105, 0xbfb8aa3b, v105
	v_exp_f32_e32 v105, v105
	s_waitcnt vmcnt(0)
	v_mul_f32_e32 v124, v126, v124
	v_add_f32_e32 v105, 1.0, v105
	v_rcp_f32_e32 v105, v105
	v_lshl_add_u64 v[126:127], v[244:245], 0, v[120:121]
	v_mul_f32_e32 v105, v124, v105
	v_cvt_pk_bf16_f32 v105, v105, s0
	global_store_short v[122:123], v105, off offset:128
	global_load_ushort v105, v[126:127], off
	s_waitcnt vmcnt(0)
	v_lshlrev_b32_e32 v105, 16, v105
	global_load_dword v124, v[110:111], off offset:384
	v_mul_f32_e32 v105, 0xbfb8aa3b, v105
	v_exp_f32_e32 v105, v105
	s_waitcnt vmcnt(0)
	v_mul_f32_e32 v103, v124, v103
	v_add_f32_e32 v105, 1.0, v105
	v_rcp_f32_e32 v105, v105
	s_nop 0
	v_mul_f32_e32 v103, v103, v105
	v_cvt_pk_bf16_f32 v103, v103, s0
	global_store_short v[122:123], v103, off offset:192
	ds_read_b32 v103, v238 offset:100
	ds_read_b32 v105, v239 offset:100
	v_add_u32_e32 v126, 25, v100
	v_ashrrev_i32_e32 v127, 31, v126
	v_mov_b32_e32 v244, v13
	s_waitcnt lgkmcnt(1)
	v_max_f32_e64 v103, |v103|, |v103|
	s_waitcnt lgkmcnt(0)
	v_max_f32_e32 v105, v105, v105
	v_max_f32_e32 v103, v103, v105
	v_div_scale_f32 v105, s[0:1], v103, v103, 1.0
	v_rcp_f32_e32 v122, v105
	v_mov_b32_e32 v245, v29
	v_fma_f32 v123, -v105, v122, 1.0
	v_fmac_f32_e32 v122, v123, v122
	v_div_scale_f32 v123, vcc, 1.0, v103, 1.0
	v_mul_f32_e32 v124, v123, v122
	v_fma_f32 v125, -v105, v124, v123
	v_fmac_f32_e32 v124, v125, v122
	v_fma_f32 v105, -v105, v124, v123
	v_div_fmas_f32 v105, v105, v122, v124
	v_lshlrev_b64 v[124:125], 11, v[126:127]
	v_lshl_add_u64 v[124:125], v[98:99], 0, v[124:125]
	global_load_dword v242, v[124:125], off
	global_load_dword v243, v[124:125], off offset:128
	global_load_dword v246, v[124:125], off offset:256
	global_load_dword v247, v[124:125], off offset:384
	v_div_fixup_f32 v122, v105, v103, 1.0
	v_mov_b32_e32 v124, v45
	v_mov_b32_e32 v125, v61
	s_waitcnt vmcnt(2)
	v_pk_fma_f32 v[242:243], v[244:245], v[122:123], v[242:243] op_sel_hi:[1,0,1]
	v_pk_mul_f32 v[244:245], v[242:243], v[242:243]
	s_waitcnt vmcnt(0)
	v_pk_fma_f32 v[124:125], v[124:125], v[122:123], v[246:247] op_sel_hi:[1,0,1]
	v_add_f32_e32 v103, v244, v245
	v_pk_mul_f32 v[122:123], v[124:125], v[124:125]
	v_add_f32_e32 v103, v103, v122
	v_add_f32_e32 v103, v103, v123
	v_mov_b32_e32 v105, v103
	v_mov_b32_e32 v255, v103
	s_nop 1
	v_permlane16_swap_b32_e32 v105, v255
	s_nop 1
	v_mov_b32_dpp v105, v255 quad_perm:[0,1,2,3] row_mask:0x5 bank_mask:0xf
	v_mad_i64_i32 v[122:123], s[0:1], v126, s74, v[106:107]
	v_lshl_add_u64 v[244:245], v[122:123], 0, s[96:97]
	v_lshlrev_b64 v[122:123], 10, v[126:127]
	v_add_f32_e32 v103, v103, v105
	s_nop 1
	v_mov_b32_dpp v105, v103 row_ror:8 row_mask:0xf bank_mask:0xf
	v_lshl_add_u64 v[126:127], v[244:245], 0, v[96:97]
	v_lshl_add_u64 v[122:123], s[66:67], 0, v[122:123]
	v_lshl_add_u64 v[122:123], v[122:123], 0, v[96:97]
	v_add_f32_e32 v103, v103, v105
	s_nop 1
	v_mov_b32_dpp v105, v103 row_shl:4 row_mask:0xf bank_mask:0x5
	v_mov_b32_dpp v105, v103 row_shr:4 row_mask:0xf bank_mask:0xa
	s_nop 0
	v_add_f32_e32 v103, v103, v105
	s_nop 1
	v_mov_b32_dpp v105, v103 quad_perm:[2,3,0,1] row_mask:0xf bank_mask:0xf
	v_add_f32_e32 v103, v103, v105
	s_nop 1
	v_add_f32_dpp v103, v103, v103 quad_perm:[1,0,3,2] row_mask:0xf bank_mask:0xf
	v_fmamk_f32 v103, v103, 0x3c000000, v163
	v_cmp_gt_f32_e32 vcc, s86, v103
	v_mul_f32_e32 v105, 0x4b800000, v103
	s_nop 0
	v_cndmask_b32_e32 v103, v103, v105, vcc
	v_rsq_f32_e32 v103, v103
	s_nop 0
	v_mul_f32_e32 v105, 0x45800000, v103
	v_cndmask_b32_e32 v103, v103, v105, vcc
	global_load_ushort v105, v[126:127], off
	v_mul_f32_e32 v126, v242, v103
	global_load_dword v127, v[108:109], off
	v_mul_f32_e32 v124, v124, v103
	s_waitcnt vmcnt(1)
	v_lshlrev_b32_e32 v105, 16, v105
	v_mul_f32_e32 v105, 0xbfb8aa3b, v105
	v_exp_f32_e32 v105, v105
	s_waitcnt vmcnt(0)
	v_mul_f32_e32 v126, v127, v126
	v_add_f32_e32 v105, 1.0, v105
	v_rcp_f32_e32 v105, v105
	s_nop 0
	v_mul_f32_e32 v105, v105, v126
	v_cvt_pk_bf16_f32 v105, v105, s0
	v_lshl_add_u64 v[126:127], v[244:245], 0, v[112:113]
	global_store_short v[122:123], v105, off
	global_load_ushort v105, v[126:127], off
	v_mul_f32_e32 v126, v243, v103
	global_load_dword v127, v[110:111], off offset:128
	v_mul_f32_e32 v103, v125, v103
	s_waitcnt vmcnt(1)
	v_lshlrev_b32_e32 v105, 16, v105
	v_mul_f32_e32 v105, 0xbfb8aa3b, v105
	v_exp_f32_e32 v105, v105
	s_waitcnt vmcnt(0)
	v_mul_f32_e32 v126, v127, v126
	v_add_f32_e32 v105, 1.0, v105
	v_rcp_f32_e32 v105, v105
	s_nop 0
	v_mul_f32_e32 v105, v105, v126
	v_cvt_pk_bf16_f32 v105, v105, s0
	v_lshl_add_u64 v[126:127], v[244:245], 0, v[118:119]
	global_store_short v[122:123], v105, off offset:64
	global_load_ushort v105, v[126:127], off
	s_waitcnt vmcnt(0)
	v_lshlrev_b32_e32 v105, 16, v105
	global_load_dword v126, v[110:111], off offset:256
	v_mul_f32_e32 v105, 0xbfb8aa3b, v105
	v_exp_f32_e32 v105, v105
	s_waitcnt vmcnt(0)
	v_mul_f32_e32 v124, v126, v124
	v_add_f32_e32 v105, 1.0, v105
	v_rcp_f32_e32 v105, v105
	v_lshl_add_u64 v[126:127], v[244:245], 0, v[120:121]
	v_mul_f32_e32 v105, v124, v105
	v_cvt_pk_bf16_f32 v105, v105, s0
	global_store_short v[122:123], v105, off offset:128
	global_load_ushort v105, v[126:127], off
	s_waitcnt vmcnt(0)
	v_lshlrev_b32_e32 v105, 16, v105
	global_load_dword v124, v[110:111], off offset:384
	v_mul_f32_e32 v105, 0xbfb8aa3b, v105
	v_exp_f32_e32 v105, v105
	s_waitcnt vmcnt(0)
	v_mul_f32_e32 v103, v124, v103
	v_add_f32_e32 v105, 1.0, v105
	v_rcp_f32_e32 v105, v105
	s_nop 0
	v_mul_f32_e32 v103, v103, v105
	v_cvt_pk_bf16_f32 v103, v103, s0
	global_store_short v[122:123], v103, off offset:192
	ds_read_b32 v103, v238 offset:104
	ds_read_b32 v105, v239 offset:104
	v_add_u32_e32 v126, 26, v100
	v_ashrrev_i32_e32 v127, 31, v126
	v_mov_b32_e32 v244, v14
	s_waitcnt lgkmcnt(1)
	v_max_f32_e64 v103, |v103|, |v103|
	s_waitcnt lgkmcnt(0)
	v_max_f32_e32 v105, v105, v105
	v_max_f32_e32 v103, v103, v105
	v_div_scale_f32 v105, s[0:1], v103, v103, 1.0
	v_rcp_f32_e32 v122, v105
	v_mov_b32_e32 v245, v30
	v_fma_f32 v123, -v105, v122, 1.0
	v_fmac_f32_e32 v122, v123, v122
	v_div_scale_f32 v123, vcc, 1.0, v103, 1.0
	v_mul_f32_e32 v124, v123, v122
	v_fma_f32 v125, -v105, v124, v123
	v_fmac_f32_e32 v124, v125, v122
	v_fma_f32 v105, -v105, v124, v123
	v_div_fmas_f32 v105, v105, v122, v124
	v_lshlrev_b64 v[124:125], 11, v[126:127]
	v_lshl_add_u64 v[124:125], v[98:99], 0, v[124:125]
	global_load_dword v242, v[124:125], off
	global_load_dword v243, v[124:125], off offset:128
	global_load_dword v246, v[124:125], off offset:256
	global_load_dword v247, v[124:125], off offset:384
	v_div_fixup_f32 v122, v105, v103, 1.0
	v_mov_b32_e32 v124, v46
	v_mov_b32_e32 v125, v62
	s_waitcnt vmcnt(2)
	v_pk_fma_f32 v[242:243], v[244:245], v[122:123], v[242:243] op_sel_hi:[1,0,1]
	v_pk_mul_f32 v[244:245], v[242:243], v[242:243]
	s_waitcnt vmcnt(0)
	v_pk_fma_f32 v[124:125], v[124:125], v[122:123], v[246:247] op_sel_hi:[1,0,1]
	v_add_f32_e32 v103, v244, v245
	v_pk_mul_f32 v[122:123], v[124:125], v[124:125]
	v_add_f32_e32 v103, v103, v122
	v_add_f32_e32 v103, v103, v123
	v_mov_b32_e32 v105, v103
	v_mov_b32_e32 v255, v103
	s_nop 1
	v_permlane16_swap_b32_e32 v105, v255
	s_nop 1
	v_mov_b32_dpp v105, v255 quad_perm:[0,1,2,3] row_mask:0x5 bank_mask:0xf
	v_mad_i64_i32 v[122:123], s[0:1], v126, s74, v[106:107]
	v_lshl_add_u64 v[244:245], v[122:123], 0, s[96:97]
	v_lshlrev_b64 v[122:123], 10, v[126:127]
	v_add_f32_e32 v103, v103, v105
	s_nop 1
	v_mov_b32_dpp v105, v103 row_ror:8 row_mask:0xf bank_mask:0xf
	v_lshl_add_u64 v[126:127], v[244:245], 0, v[96:97]
	v_lshl_add_u64 v[122:123], s[66:67], 0, v[122:123]
	v_lshl_add_u64 v[122:123], v[122:123], 0, v[96:97]
	v_add_f32_e32 v103, v103, v105
	s_nop 1
	v_mov_b32_dpp v105, v103 row_shl:4 row_mask:0xf bank_mask:0x5
	v_mov_b32_dpp v105, v103 row_shr:4 row_mask:0xf bank_mask:0xa
	s_nop 0
	v_add_f32_e32 v103, v103, v105
	s_nop 1
	v_mov_b32_dpp v105, v103 quad_perm:[2,3,0,1] row_mask:0xf bank_mask:0xf
	v_add_f32_e32 v103, v103, v105
	s_nop 1
	v_add_f32_dpp v103, v103, v103 quad_perm:[1,0,3,2] row_mask:0xf bank_mask:0xf
	v_fmamk_f32 v103, v103, 0x3c000000, v163
	v_cmp_gt_f32_e32 vcc, s86, v103
	v_mul_f32_e32 v105, 0x4b800000, v103
	s_nop 0
	v_cndmask_b32_e32 v103, v103, v105, vcc
	v_rsq_f32_e32 v103, v103
	s_nop 0
	v_mul_f32_e32 v105, 0x45800000, v103
	v_cndmask_b32_e32 v103, v103, v105, vcc
	global_load_ushort v105, v[126:127], off
	v_mul_f32_e32 v126, v242, v103
	global_load_dword v127, v[108:109], off
	v_mul_f32_e32 v124, v124, v103
	s_waitcnt vmcnt(1)
	v_lshlrev_b32_e32 v105, 16, v105
	v_mul_f32_e32 v105, 0xbfb8aa3b, v105
	v_exp_f32_e32 v105, v105
	s_waitcnt vmcnt(0)
	v_mul_f32_e32 v126, v127, v126
	v_add_f32_e32 v105, 1.0, v105
	v_rcp_f32_e32 v105, v105
	s_nop 0
	v_mul_f32_e32 v105, v105, v126
	v_cvt_pk_bf16_f32 v105, v105, s0
	v_lshl_add_u64 v[126:127], v[244:245], 0, v[112:113]
	global_store_short v[122:123], v105, off
	global_load_ushort v105, v[126:127], off
	v_mul_f32_e32 v126, v243, v103
	global_load_dword v127, v[110:111], off offset:128
	v_mul_f32_e32 v103, v125, v103
	s_waitcnt vmcnt(1)
	v_lshlrev_b32_e32 v105, 16, v105
	v_mul_f32_e32 v105, 0xbfb8aa3b, v105
	v_exp_f32_e32 v105, v105
	s_waitcnt vmcnt(0)
	v_mul_f32_e32 v126, v127, v126
	v_add_f32_e32 v105, 1.0, v105
	v_rcp_f32_e32 v105, v105
	s_nop 0
	v_mul_f32_e32 v105, v105, v126
	v_cvt_pk_bf16_f32 v105, v105, s0
	v_lshl_add_u64 v[126:127], v[244:245], 0, v[118:119]
	global_store_short v[122:123], v105, off offset:64
	global_load_ushort v105, v[126:127], off
	s_waitcnt vmcnt(0)
	v_lshlrev_b32_e32 v105, 16, v105
	global_load_dword v126, v[110:111], off offset:256
	v_mul_f32_e32 v105, 0xbfb8aa3b, v105
	v_exp_f32_e32 v105, v105
	s_waitcnt vmcnt(0)
	v_mul_f32_e32 v124, v126, v124
	v_add_f32_e32 v105, 1.0, v105
	v_rcp_f32_e32 v105, v105
	v_lshl_add_u64 v[126:127], v[244:245], 0, v[120:121]
	v_mul_f32_e32 v105, v124, v105
	v_cvt_pk_bf16_f32 v105, v105, s0
	global_store_short v[122:123], v105, off offset:128
	global_load_ushort v105, v[126:127], off
	s_waitcnt vmcnt(0)
	v_lshlrev_b32_e32 v105, 16, v105
	global_load_dword v124, v[110:111], off offset:384
	v_mul_f32_e32 v105, 0xbfb8aa3b, v105
	v_exp_f32_e32 v105, v105
	s_waitcnt vmcnt(0)
	v_mul_f32_e32 v103, v124, v103
	v_add_f32_e32 v105, 1.0, v105
	v_rcp_f32_e32 v105, v105
	s_nop 0
	v_mul_f32_e32 v103, v103, v105
	v_cvt_pk_bf16_f32 v103, v103, s0
	global_store_short v[122:123], v103, off offset:192
	v_add_u32_e32 v122, 27, v100
	v_ashrrev_i32_e32 v123, 31, v122
	v_lshlrev_b64 v[124:125], 11, v[122:123]
	v_lshl_add_u64 v[124:125], v[98:99], 0, v[124:125]
	global_load_dword v126, v[124:125], off
	global_load_dword v127, v[124:125], off offset:128
	global_load_dword v242, v[124:125], off offset:256
	global_load_dword v243, v[124:125], off offset:384
	v_mad_i64_i32 v[106:107], s[0:1], v122, s74, v[106:107]
	v_lshl_add_u64 v[106:107], v[106:107], 0, s[96:97]
	v_lshl_add_u64 v[124:125], v[106:107], 0, v[96:97]
	global_load_ushort v103, v[124:125], off
	v_lshl_add_u64 v[112:113], v[106:107], 0, v[112:113]
	v_lshl_add_u64 v[118:119], v[106:107], 0, v[118:119]
	v_lshl_add_u64 v[106:107], v[106:107], 0, v[120:121]
	global_load_ushort v105, v[112:113], off
	global_load_ushort v118, v[118:119], off
	global_load_ushort v119, v[106:107], off
	global_load_dword v120, v[108:109], off
	global_load_dword v121, v[110:111], off offset:128
	global_load_dword v124, v[110:111], off offset:256
	global_load_dword v125, v[110:111], off offset:384
	ds_read_b32 v109, v239 offset:108
	ds_read_b32 v110, v238 offset:108
	v_mov_b32_e32 v106, v15
	v_mov_b32_e32 v107, v31
	v_mov_b32_e32 v108, v47
	s_waitcnt lgkmcnt(1)
	v_max_f32_e32 v109, v109, v109
	s_waitcnt lgkmcnt(0)
	v_max_f32_e64 v110, |v110|, |v110|
	v_max_f32_e32 v110, v110, v109
	v_div_scale_f32 v111, s[0:1], v110, v110, 1.0
	v_rcp_f32_e32 v112, v111
	v_div_scale_f32 v113, vcc, 1.0, v110, 1.0
	v_mov_b32_e32 v109, v63
	v_fma_f32 v238, -v111, v112, 1.0
	v_fmac_f32_e32 v112, v238, v112
	v_mul_f32_e32 v238, v113, v112
	v_fma_f32 v239, -v111, v238, v113
	v_fmac_f32_e32 v238, v239, v112
	v_fma_f32 v111, -v111, v238, v113
	v_div_fmas_f32 v111, v111, v112, v238
	v_div_fixup_f32 v110, v111, v110, 1.0
	s_waitcnt vmcnt(10)
	v_pk_fma_f32 v[106:107], v[106:107], v[110:111], v[126:127] op_sel_hi:[1,0,1]
	s_waitcnt vmcnt(8)
	v_pk_fma_f32 v[108:109], v[108:109], v[110:111], v[242:243] op_sel_hi:[1,0,1]
	v_pk_mul_f32 v[110:111], v[106:107], v[106:107]
	v_pk_mul_f32 v[112:113], v[108:109], v[108:109]
	v_add_f32_e32 v110, v110, v111
	v_add_f32_e32 v110, v110, v112
	v_add_f32_e32 v112, v110, v113
	v_mov_b32_e32 v113, v112
	v_mov_b32_e32 v255, v112
	s_nop 1
	v_permlane16_swap_b32_e32 v113, v255
	v_lshlrev_b64 v[110:111], 10, v[122:123]
	v_lshl_add_u64 v[110:111], s[66:67], 0, v[110:111]
	v_lshl_add_u64 v[110:111], v[110:111], 0, v[96:97]
	s_waitcnt vmcnt(7)
	v_lshlrev_b32_e32 v96, 16, v103
	v_add_f32_e32 v103, v113, v255
	s_nop 1
	v_mov_b32_dpp v112, v103 row_ror:8 row_mask:0xf bank_mask:0xf
	s_waitcnt vmcnt(5)
	v_lshlrev_b32_e32 v113, 16, v118
	s_waitcnt vmcnt(4)
	v_lshlrev_b32_e32 v118, 16, v119
	v_lshlrev_b32_e32 v105, 16, v105
	v_mul_f32_e32 v96, 0xbfb8aa3b, v96
	v_add_f32_e32 v103, v103, v112
	s_nop 1
	v_mov_b32_dpp v112, v103 row_shl:4 row_mask:0xf bank_mask:0x5
	v_mov_b32_dpp v112, v103 row_shr:4 row_mask:0xf bank_mask:0xa
	v_mul_f32_e32 v113, 0xbfb8aa3b, v113
	v_mul_f32_e32 v118, 0xbfb8aa3b, v118
	v_mul_f32_e32 v105, 0xbfb8aa3b, v105
	v_exp_f32_e32 v96, v96
	v_add_f32_e32 v103, v103, v112
	s_nop 1
	v_mov_b32_dpp v112, v103 quad_perm:[2,3,0,1] row_mask:0xf bank_mask:0xf
	v_exp_f32_e32 v113, v113
	v_exp_f32_e32 v118, v118
	v_exp_f32_e32 v105, v105
	v_add_f32_e32 v96, 1.0, v96
	v_add_f32_e32 v103, v103, v112
	v_add_f32_e32 v113, 1.0, v113
	v_add_f32_e32 v118, 1.0, v118
	v_add_f32_e32 v105, 1.0, v105
	v_rcp_f32_e32 v96, v96
	v_add_f32_dpp v103, v103, v103 quad_perm:[1,0,3,2] row_mask:0xf bank_mask:0xf
	v_fmamk_f32 v103, v103, 0x3c000000, v163
	v_mul_f32_e32 v112, 0x4b800000, v103
	v_cmp_gt_f32_e32 vcc, s86, v103
	v_rcp_f32_e32 v105, v105
	s_nop 0
	v_cndmask_b32_e32 v103, v103, v112, vcc
	v_rsq_f32_e32 v103, v103
	v_rcp_f32_e32 v112, v113
	v_rcp_f32_e32 v113, v118
	v_mul_f32_e32 v118, 0x45800000, v103
	v_cndmask_b32_e32 v103, v103, v118, vcc
	v_mul_f32_e32 v106, v106, v103
	v_mul_f32_e32 v107, v107, v103
	v_mul_f32_e32 v108, v108, v103
	v_mul_f32_e32 v103, v109, v103
	s_waitcnt vmcnt(3)
	v_mul_f32_e32 v106, v120, v106
	s_waitcnt vmcnt(2)
	v_mul_f32_e32 v107, v121, v107
	s_waitcnt vmcnt(1)
	v_mul_f32_e32 v108, v124, v108
	s_waitcnt vmcnt(0)
	v_mul_f32_e32 v103, v125, v103
	v_mul_f32_e32 v96, v96, v106
	v_mul_f32_e32 v105, v105, v107
	v_mul_f32_e32 v106, v108, v112
	v_mul_f32_e32 v103, v103, v113
	v_cvt_pk_bf16_f32 v96, v96, s0
	v_cvt_pk_bf16_f32 v105, v105, s0
	v_cvt_pk_bf16_f32 v106, v106, s0
	v_cvt_pk_bf16_f32 v103, v103, s0
	global_store_short v[110:111], v96, off
	global_store_short v[110:111], v105, off offset:64
	global_store_short v[110:111], v106, off offset:128
	global_store_short v[110:111], v103, off offset:192
	s_cbranch_execnz .LBB0_927
	s_branch .LBB0_1111

.LBB0_1170:
	v_lshl_add_u64 v[120:121], s[92:93], 0, v[102:103]
	v_add_co_u32_e32 v120, vcc, 0xcf01000, v120
	s_waitcnt lgkmcnt(0)
	s_nop 0
	v_addc_co_u32_e32 v121, vcc, 0, v121, vcc
	s_barrier
	v_lshl_add_u64 v[128:129], s[92:93], 0, v[100:101]
	v_add_co_u32_e32 v128, vcc, 0xcf01000, v128
	s_nop 1
	v_addc_co_u32_e32 v129, vcc, 0, v129, vcc
	global_load_dwordx2 v[136:137], v[120:121], off offset:3584
	global_load_dwordx2 v[138:139], v[120:121], off offset:3600
	global_load_dwordx2 v[140:141], v[120:121], off offset:3616
	global_load_dwordx2 v[142:143], v[120:121], off offset:3632
	global_load_dwordx2 v[144:145], v[128:129], off offset:3584
	global_load_dwordx2 v[146:147], v[128:129], off offset:3600
	global_load_dwordx2 v[148:149], v[128:129], off offset:3616
	global_load_dwordx2 v[150:151], v[128:129], off offset:3632
	s_mov_b32 s4, 0xcf01000
	s_add_u32 s42, s42, 0x100000
	s_addc_u32 s43, s43, 0
	s_add_u32 s40, s40, 0x1200000
	v_lshl_add_u64 v[102:103], v[102:103], 0, s[36:37]
	s_addc_u32 s41, s41, 0
	s_mov_b64 s[38:39], 0
	s_waitcnt vmcnt(7)
	v_mov_b64_e32 v[122:123], v[136:137]
	v_lshlrev_b32_e32 v96, 16, v122
	v_mul_f32_e32 v96, 0xbfb8aa3b, v96
	v_exp_f32_e32 v96, v96
	s_nop 0
	v_add_f32_e32 v96, 1.0, v96
	v_rcp_f32_e32 v124, v96
	v_and_b32_e32 v96, 0xffff0000, v122
	v_mul_f32_e32 v96, 0xbfb8aa3b, v96
	v_exp_f32_e32 v96, v96
	s_nop 0
	v_add_f32_e32 v96, 1.0, v96
	v_rcp_f32_e32 v125, v96
	s_nop 0
	v_pk_fma_f32 v[116:117], v[16:17], v[124:125], v[116:117]
	v_lshlrev_b32_e32 v16, 16, v123
	v_and_b32_e32 v17, 0xffff0000, v123
	v_mul_f32_e32 v16, 0xbfb8aa3b, v16
	v_mul_f32_e32 v17, 0xbfb8aa3b, v17
	v_exp_f32_e32 v16, v16
	v_exp_f32_e32 v17, v17
	v_add_f32_e32 v16, 1.0, v16
	v_add_f32_e32 v17, 1.0, v17
	v_rcp_f32_e32 v16, v16
	v_rcp_f32_e32 v17, v17
	s_nop 0
	v_pk_fma_f32 v[118:119], v[18:19], v[16:17], v[118:119]
	s_waitcnt vmcnt(6)
	v_mov_b64_e32 v[16:17], v[138:139]
	v_lshlrev_b32_e32 v18, 16, v16
	v_and_b32_e32 v16, 0xffff0000, v16
	v_mul_f32_e32 v16, 0xbfb8aa3b, v16
	v_exp_f32_e32 v16, v16
	v_mul_f32_e32 v18, 0xbfb8aa3b, v18
	v_exp_f32_e32 v18, v18
	v_add_f32_e32 v16, 1.0, v16
	v_rcp_f32_e32 v19, v16
	v_lshlrev_b32_e32 v16, 16, v17
	v_and_b32_e32 v17, 0xffff0000, v17
	v_mul_f32_e32 v16, 0xbfb8aa3b, v16
	v_mul_f32_e32 v17, 0xbfb8aa3b, v17
	v_exp_f32_e32 v16, v16
	v_exp_f32_e32 v17, v17
	v_add_f32_e32 v18, 1.0, v18
	v_rcp_f32_e32 v18, v18
	v_add_f32_e32 v16, 1.0, v16
	v_add_f32_e32 v17, 1.0, v17
	v_rcp_f32_e32 v16, v16
	v_rcp_f32_e32 v17, v17
	v_pk_fma_f32 v[112:113], v[20:21], v[18:19], v[112:113]
	v_pk_fma_f32 v[114:115], v[22:23], v[16:17], v[114:115]
	s_waitcnt vmcnt(5)
	v_mov_b64_e32 v[16:17], v[140:141]
	v_lshlrev_b32_e32 v18, 16, v16
	v_and_b32_e32 v16, 0xffff0000, v16
	v_mul_f32_e32 v16, 0xbfb8aa3b, v16
	v_exp_f32_e32 v16, v16
	v_mul_f32_e32 v18, 0xbfb8aa3b, v18
	v_exp_f32_e32 v18, v18
	v_add_f32_e32 v16, 1.0, v16
	v_rcp_f32_e32 v19, v16
	v_lshlrev_b32_e32 v16, 16, v17
	v_and_b32_e32 v17, 0xffff0000, v17
	v_mul_f32_e32 v16, 0xbfb8aa3b, v16
	v_mul_f32_e32 v17, 0xbfb8aa3b, v17
	v_exp_f32_e32 v16, v16
	v_exp_f32_e32 v17, v17
	v_add_f32_e32 v18, 1.0, v18
	v_rcp_f32_e32 v18, v18
	v_add_f32_e32 v16, 1.0, v16
	v_add_f32_e32 v17, 1.0, v17
	v_rcp_f32_e32 v16, v16
	v_rcp_f32_e32 v17, v17
	v_pk_fma_f32 v[108:109], v[24:25], v[18:19], v[108:109]
	v_pk_fma_f32 v[110:111], v[26:27], v[16:17], v[110:111]
	s_waitcnt vmcnt(4)
	v_mov_b64_e32 v[16:17], v[142:143]
	v_lshlrev_b32_e32 v18, 16, v16
	v_and_b32_e32 v16, 0xffff0000, v16
	v_mul_f32_e32 v16, 0xbfb8aa3b, v16
	v_exp_f32_e32 v16, v16
	v_mul_f32_e32 v18, 0xbfb8aa3b, v18
	v_exp_f32_e32 v18, v18
	v_add_f32_e32 v16, 1.0, v16
	v_rcp_f32_e32 v19, v16
	v_lshlrev_b32_e32 v16, 16, v17
	v_and_b32_e32 v17, 0xffff0000, v17
	v_mul_f32_e32 v16, 0xbfb8aa3b, v16
	v_mul_f32_e32 v17, 0xbfb8aa3b, v17
	v_exp_f32_e32 v16, v16
	v_exp_f32_e32 v17, v17
	v_add_f32_e32 v18, 1.0, v18
	v_rcp_f32_e32 v18, v18
	v_add_f32_e32 v16, 1.0, v16
	v_add_f32_e32 v17, 1.0, v17
	v_rcp_f32_e32 v16, v16
	v_rcp_f32_e32 v17, v17
	v_pk_fma_f32 v[106:107], v[28:29], v[18:19], v[106:107]
	v_pk_fma_f32 v[104:105], v[30:31], v[16:17], v[104:105]
	v_lshl_add_u64 v[16:17], s[92:93], 0, v[100:101]
	v_add_co_u32_e32 v16, vcc, s4, v16
	v_lshl_add_u64 v[100:101], v[100:101], 0, s[36:37]
	s_nop 0
	v_addc_co_u32_e32 v17, vcc, 0, v17, vcc
	s_waitcnt vmcnt(3)
	v_mov_b64_e32 v[18:19], v[144:145]
	v_lshlrev_b32_e32 v20, 16, v18
	v_and_b32_e32 v18, 0xffff0000, v18
	v_mul_f32_e32 v20, 0xbfb8aa3b, v20
	v_mul_f32_e32 v18, 0xbfb8aa3b, v18
	v_exp_f32_e32 v20, v20
	v_exp_f32_e32 v18, v18
	v_add_f32_e32 v20, 1.0, v20
	v_add_f32_e32 v18, 1.0, v18
	v_rcp_f32_e32 v20, v20
	v_rcp_f32_e32 v21, v18
	s_nop 0
	v_pk_fma_f32 v[92:93], v[0:1], v[20:21], v[92:93]
	v_lshlrev_b32_e32 v0, 16, v19
	v_and_b32_e32 v1, 0xffff0000, v19
	v_mul_f32_e32 v0, 0xbfb8aa3b, v0
	v_mul_f32_e32 v1, 0xbfb8aa3b, v1
	v_exp_f32_e32 v0, v0
	v_exp_f32_e32 v1, v1
	v_add_f32_e32 v0, 1.0, v0
	v_add_f32_e32 v1, 1.0, v1
	v_rcp_f32_e32 v0, v0
	v_rcp_f32_e32 v1, v1
	s_nop 0
	v_pk_fma_f32 v[94:95], v[2:3], v[0:1], v[94:95]
	s_waitcnt vmcnt(2)
	v_mov_b64_e32 v[0:1], v[146:147]
	v_lshlrev_b32_e32 v2, 16, v0
	v_and_b32_e32 v0, 0xffff0000, v0
	v_mul_f32_e32 v0, 0xbfb8aa3b, v0
	v_exp_f32_e32 v0, v0
	v_mul_f32_e32 v2, 0xbfb8aa3b, v2
	v_exp_f32_e32 v2, v2
	v_add_f32_e32 v0, 1.0, v0
	v_rcp_f32_e32 v3, v0
	v_lshlrev_b32_e32 v0, 16, v1
	v_and_b32_e32 v1, 0xffff0000, v1
	v_mul_f32_e32 v0, 0xbfb8aa3b, v0
	v_mul_f32_e32 v1, 0xbfb8aa3b, v1
	v_exp_f32_e32 v0, v0
	v_exp_f32_e32 v1, v1
	v_add_f32_e32 v2, 1.0, v2
	v_rcp_f32_e32 v2, v2
	v_add_f32_e32 v0, 1.0, v0
	v_add_f32_e32 v1, 1.0, v1
	v_rcp_f32_e32 v0, v0
	v_rcp_f32_e32 v1, v1
	v_pk_fma_f32 v[88:89], v[4:5], v[2:3], v[88:89]
	v_pk_fma_f32 v[90:91], v[6:7], v[0:1], v[90:91]
	s_waitcnt vmcnt(1)
	v_mov_b64_e32 v[0:1], v[148:149]
	v_lshlrev_b32_e32 v2, 16, v0
	v_and_b32_e32 v0, 0xffff0000, v0
	v_mul_f32_e32 v0, 0xbfb8aa3b, v0
	v_exp_f32_e32 v0, v0
	v_mul_f32_e32 v2, 0xbfb8aa3b, v2
	v_exp_f32_e32 v2, v2
	v_add_f32_e32 v0, 1.0, v0
	v_rcp_f32_e32 v3, v0
	v_lshlrev_b32_e32 v0, 16, v1
	v_and_b32_e32 v1, 0xffff0000, v1
	v_mul_f32_e32 v0, 0xbfb8aa3b, v0
	v_mul_f32_e32 v1, 0xbfb8aa3b, v1
	v_exp_f32_e32 v0, v0
	v_exp_f32_e32 v1, v1
	v_add_f32_e32 v2, 1.0, v2
	v_rcp_f32_e32 v2, v2
	v_add_f32_e32 v0, 1.0, v0
	v_add_f32_e32 v1, 1.0, v1
	v_rcp_f32_e32 v0, v0
	v_rcp_f32_e32 v1, v1
	v_pk_fma_f32 v[84:85], v[8:9], v[2:3], v[84:85]
	v_pk_fma_f32 v[86:87], v[10:11], v[0:1], v[86:87]
	s_waitcnt vmcnt(0)
	v_mov_b64_e32 v[0:1], v[150:151]
	v_lshlrev_b32_e32 v2, 16, v0
	v_and_b32_e32 v0, 0xffff0000, v0
	v_mul_f32_e32 v0, 0xbfb8aa3b, v0
	v_exp_f32_e32 v0, v0
	v_mul_f32_e32 v2, 0xbfb8aa3b, v2
	v_exp_f32_e32 v2, v2
	v_add_f32_e32 v0, 1.0, v0
	v_rcp_f32_e32 v3, v0
	v_lshlrev_b32_e32 v0, 16, v1
	v_and_b32_e32 v1, 0xffff0000, v1
	v_mul_f32_e32 v0, 0xbfb8aa3b, v0
	v_mul_f32_e32 v1, 0xbfb8aa3b, v1
	v_exp_f32_e32 v0, v0
	v_exp_f32_e32 v1, v1
	v_add_f32_e32 v2, 1.0, v2
	v_rcp_f32_e32 v2, v2
	v_add_f32_e32 v0, 1.0, v0
	v_add_f32_e32 v1, 1.0, v1
	v_rcp_f32_e32 v0, v0
	v_rcp_f32_e32 v1, v1
	v_pk_fma_f32 v[82:83], v[12:13], v[2:3], v[82:83]
	v_pk_fma_f32 v[80:81], v[14:15], v[0:1], v[80:81]
	v_add_co_u32_e64 v0, s[44:45], s7, 1
	s_nop 0
	v_readfirstlane_b32 s7, v0
	s_and_b64 vcc, exec, s[44:45]
	s_cbranch_vccnz .LBB0_1166

.LBB0_1173:
	v_mov_b32_e32 v3, v162
	s_add_u32 s54, s92, s40
	v_ashrrev_i32_e32 v4, 3, v3
	v_lshlrev_b32_e32 v0, 3, v3
	v_ashrrev_i32_e32 v5, 31, v4
	v_and_b32_e32 v2, 56, v0
	v_lshlrev_b64 v[0:1], 10, v[4:5]
	v_and_b32_e32 v5, 7, v3
	v_lshl_or_b32 v6, v5, 4, v0
	v_mov_b32_e32 v7, v1
	s_addc_u32 s55, s93, s41
	v_lshl_add_u64 v[126:127], s[54:55], 0, v[6:7]
	s_add_u32 s54, s92, s42
	s_addc_u32 s55, s93, s43
	v_lshl_add_u64 v[130:131], s[54:55], 0, v[6:7]
	v_mad_u64_u32 v[4:5], s[54:55], v4, s84, v[2:3]
	s_andn2_b64 vcc, exec, s[38:39]
	v_lshl_add_u32 v99, v4, 1, 0
	s_cbranch_vccnz .LBB0_1175
	v_add_co_u32_e32 v28, vcc, 0x1f6e0000, v126
	s_nop 1
	v_addc_co_u32_e32 v29, vcc, 0, v127, vcc
	v_add_co_u32_e32 v30, vcc, 0x1f6e8000, v126
	global_load_dwordx4 v[4:7], v[28:29], off
	s_nop 0
	v_addc_co_u32_e32 v31, vcc, 0, v127, vcc
	v_add_co_u32_e32 v40, vcc, 0x1f6f0000, v126
	global_load_dwordx4 v[8:11], v[30:31], off
	s_nop 0
	v_addc_co_u32_e32 v41, vcc, 0, v127, vcc
	v_add_co_u32_e32 v44, vcc, 0x1f6f8000, v126
	global_load_dwordx4 v[12:15], v[40:41], off
	s_nop 0
	v_addc_co_u32_e32 v45, vcc, 0, v127, vcc
	v_add_co_u32_e32 v48, vcc, 0x1f1e0000, v130
	global_load_dwordx4 v[16:19], v[44:45], off
	s_nop 0
	v_addc_co_u32_e32 v49, vcc, 0, v131, vcc
	v_add_co_u32_e32 v52, vcc, 0x1f1e8000, v130
	global_load_dwordx4 v[20:23], v[48:49], off
	s_nop 0
	v_addc_co_u32_e32 v53, vcc, 0, v131, vcc
	global_load_dwordx4 v[24:27], v[52:53], off
	s_waitcnt vmcnt(5)
	ds_write_b128 v99, v[4:7]
	s_waitcnt vmcnt(4)
	ds_write_b128 v99, v[8:11] offset:4608
	s_waitcnt vmcnt(3)
	ds_write_b128 v99, v[12:15] offset:9216
	s_waitcnt vmcnt(2)
	ds_write_b128 v99, v[16:19] offset:13824
	s_waitcnt vmcnt(1)
	ds_write_b128 v99, v[20:23] offset:36864
	s_waitcnt vmcnt(0)
	ds_write_b128 v99, v[24:27] offset:41472
	global_load_dwordx4 v[56:59], v[28:29], off offset:128
	global_load_dwordx4 v[60:63], v[30:31], off offset:128
	global_load_dwordx4 v[64:67], v[40:41], off offset:128
	global_load_dwordx4 v[72:75], v[44:45], off offset:128
	global_load_dwordx4 v[68:71], v[48:49], off offset:128
	global_load_dwordx4 v[76:79], v[52:53], off offset:128
	global_load_dwordx4 v[32:35], v[28:29], off offset:256
	global_load_dwordx4 v[36:39], v[30:31], off offset:256
	global_load_dwordx4 v[40:43], v[40:41], off offset:256
	global_load_dwordx4 v[44:47], v[44:45], off offset:256
	global_load_dwordx4 v[48:51], v[48:49], off offset:256
	global_load_dwordx4 v[52:55], v[52:53], off offset:256
	s_waitcnt lgkmcnt(0)
	s_barrier

.LBB0_1179:
	s_waitcnt lgkmcnt(0)
	s_barrier
	s_setprio 1
	ds_read_b128 v[212:215], v135 offset:55296
	ds_read_b128 v[216:219], v96 offset:18432
	ds_read_b128 v[220:223], v96 offset:23040
	ds_read_b128 v[224:227], v135 offset:55328
	ds_read_b128 v[228:231], v96 offset:18464
	ds_read_b128 v[244:247], v96 offset:23072
	ds_read_b128 v[252:255], v135 offset:55360
	s_waitcnt lgkmcnt(5)
	v_mfma_f32_32x32x16_bf16 v[16:31], v[212:215], v[216:219], v[16:31]
	ds_read_b128 v[216:219], v96 offset:18496
	s_waitcnt lgkmcnt(5)
	v_mfma_f32_32x32x16_bf16 v[0:15], v[212:215], v[220:223], v[0:15]
	ds_read_b128 v[212:215], v96 offset:23104
	ds_read_b128 v[220:223], v135 offset:55392
	s_waitcnt lgkmcnt(5)
	v_mfma_f32_32x32x16_bf16 v[16:31], v[224:227], v[228:231], v[16:31]
	ds_read_b128 v[228:231], v96 offset:18528
	s_waitcnt lgkmcnt(5)
	v_mfma_f32_32x32x16_bf16 v[0:15], v[224:227], v[244:247], v[0:15]
	ds_read_b128 v[224:227], v96 offset:23136
	s_waitcnt lgkmcnt(4)
	v_mfma_f32_32x32x16_bf16 v[16:31], v[252:255], v[216:219], v[16:31]
	s_waitcnt lgkmcnt(3)
	v_mfma_f32_32x32x16_bf16 v[0:15], v[252:255], v[212:215], v[0:15]
	s_waitcnt lgkmcnt(1)
	v_mfma_f32_32x32x16_bf16 v[16:31], v[220:223], v[228:231], v[16:31]
	s_waitcnt lgkmcnt(0)
	v_mfma_f32_32x32x16_bf16 v[0:15], v[220:223], v[224:227], v[0:15]
	s_setprio 0
	s_and_b64 vcc, exec, s[38:39]
	s_cbranch_vccnz .LBB0_1170
	ds_write_b128 v99, v[32:35]
	ds_write_b128 v99, v[36:39] offset:4608
	ds_write_b128 v99, v[40:43] offset:9216
	ds_write_b128 v99, v[44:47] offset:13824
	ds_write_b128 v99, v[48:51] offset:36864
	ds_write_b128 v99, v[52:55] offset:41472
	v_add_co_u32_e32 v36, vcc, 0x8000, v122
	global_load_dwordx4 v[32:35], v[122:123], off offset:256
	s_nop 0
	v_addc_co_u32_e32 v37, vcc, 0, v123, vcc
	v_add_co_u32_e32 v40, vcc, 0x10000, v122
	s_nop 1
	v_addc_co_u32_e32 v41, vcc, 0, v123, vcc
	v_add_co_u32_e32 v44, vcc, 0x18000, v122
	global_load_dwordx4 v[36:39], v[36:37], off offset:256
	s_nop 0
	global_load_dwordx4 v[40:43], v[40:41], off offset:256
	v_addc_co_u32_e32 v45, vcc, 0, v123, vcc
	v_add_co_u32_e32 v52, vcc, 0x8000, v120
	global_load_dwordx4 v[44:47], v[44:45], off offset:256
	global_load_dwordx4 v[48:51], v[120:121], off offset:256
	v_addc_co_u32_e32 v53, vcc, 0, v121, vcc
	global_load_dwordx4 v[52:55], v[52:53], off offset:256
	s_branch .LBB0_1170

.LBB0_1232:
	s_lshl_b32 s3, s6, 7
	s_min_i32 s6, s3, 0x4000
	s_ashr_i32 s6, s6, 11
	s_mul_hi_i32 s7, s6, 0x9000
	s_mul_i32 s6, s6, 0x9000
	s_add_u32 s6, s16, s6
	v_add_u32_e32 v98, s3, v169
	s_addc_u32 s7, s17, s7
	v_lshl_or_b32 v134, s2, 7, v176
	v_ashrrev_i32_e32 v99, 31, v98
	s_add_u32 s6, s6, 0x5000
	v_lshlrev_b64 v[132:133], 12, v[98:99]
	v_ashrrev_i32_e32 v135, 31, v134
	v_or_b32_e32 v98, 32, v98
	s_addc_u32 s7, s7, 0
	v_lshlrev_b64 v[136:137], 2, v[134:135]
	v_ashrrev_i32_e32 v99, 31, v98
	v_lshl_add_u64 v[138:139], s[6:7], 0, v[136:137]
	v_lshl_add_u64 v[136:137], s[92:93], 0, v[136:137]
	v_lshlrev_b64 v[98:99], 12, v[98:99]
	s_waitcnt lgkmcnt(0)
	s_barrier
	v_lshl_add_u64 v[132:133], v[136:137], 0, v[132:133]
	v_lshl_add_u64 v[98:99], v[136:137], 0, v[98:99]
	global_load_dwordx4 v[136:139], v[138:139], off
	s_nop 0
	global_load_dwordx4 v[140:143], v[132:133], off
	global_load_dwordx4 v[144:147], v[98:99], off
	s_mov_b64 s[44:45], 0
	s_and_b64 vcc, exec, s[0:1]
	s_mov_b32 s3, s46
	s_waitcnt vmcnt(1)
	v_pk_fma_f32 v[32:33], v[32:33], v[136:137], v[140:141]
	v_pk_fma_f32 v[34:35], v[34:35], v[138:139], v[142:143]
	global_store_dwordx4 v[132:133], v[32:35], off
	s_waitcnt vmcnt(1)
	v_pk_fma_f32 v[48:49], v[48:49], v[136:137], v[144:145]
	v_pk_fma_f32 v[50:51], v[50:51], v[138:139], v[146:147]
	v_or_b32_e32 v32, 8, v134
	v_ashrrev_i32_e32 v33, 31, v32
	global_store_dwordx4 v[98:99], v[48:51], off
	v_lshl_add_u64 v[32:33], v[32:33], 2, s[6:7]
	global_load_dwordx4 v[32:35], v[32:33], off
	global_load_dwordx4 v[48:51], v[132:133], off offset:32
	global_load_dwordx4 v[136:139], v[98:99], off offset:32
	s_waitcnt vmcnt(1)
	v_pk_fma_f32 v[36:37], v[36:37], v[32:33], v[48:49]
	s_waitcnt vmcnt(0)
	v_pk_fma_f32 v[32:33], v[52:53], v[32:33], v[136:137]
	v_pk_fma_f32 v[38:39], v[38:39], v[34:35], v[50:51]
	v_pk_fma_f32 v[34:35], v[54:55], v[34:35], v[138:139]
	global_store_dwordx4 v[98:99], v[32:35], off offset:32
	global_store_dwordx4 v[132:133], v[36:39], off offset:32
	s_nop 0
	v_or_b32_e32 v32, 16, v134
	v_ashrrev_i32_e32 v33, 31, v32
	v_lshl_add_u64 v[32:33], v[32:33], 2, s[6:7]
	global_load_dwordx4 v[32:35], v[32:33], off
	global_load_dwordx4 v[36:39], v[132:133], off offset:64
	global_load_dwordx4 v[48:51], v[98:99], off offset:64
	s_waitcnt vmcnt(1)
	v_pk_fma_f32 v[36:37], v[40:41], v[32:33], v[36:37]
	s_waitcnt vmcnt(0)
	v_pk_fma_f32 v[32:33], v[56:57], v[32:33], v[48:49]
	v_pk_fma_f32 v[38:39], v[42:43], v[34:35], v[38:39]
	v_pk_fma_f32 v[34:35], v[58:59], v[34:35], v[50:51]
	global_store_dwordx4 v[98:99], v[32:35], off offset:64
	global_store_dwordx4 v[132:133], v[36:39], off offset:64
	s_nop 0
	v_or_b32_e32 v32, 24, v134
	v_ashrrev_i32_e32 v33, 31, v32
	v_lshl_add_u64 v[32:33], v[32:33], 2, s[6:7]
	global_load_dwordx4 v[32:35], v[32:33], off
	global_load_dwordx4 v[36:39], v[132:133], off offset:96
	global_load_dwordx4 v[40:43], v[98:99], off offset:96
	s_waitcnt vmcnt(1)
	v_pk_fma_f32 v[36:37], v[44:45], v[32:33], v[36:37]
	s_waitcnt vmcnt(0)
	v_pk_fma_f32 v[32:33], v[60:61], v[32:33], v[40:41]
	v_pk_fma_f32 v[38:39], v[46:47], v[34:35], v[38:39]
	v_pk_fma_f32 v[34:35], v[62:63], v[34:35], v[42:43]
	global_store_dwordx4 v[98:99], v[32:35], off offset:96
	global_store_dwordx4 v[132:133], v[36:39], off offset:96
	s_nop 0
	v_or_b32_e32 v32, 32, v134
	v_ashrrev_i32_e32 v33, 31, v32
	v_lshl_add_u64 v[32:33], v[32:33], 2, s[6:7]
	global_load_dwordx4 v[32:35], v[32:33], off
	global_load_dwordx4 v[36:39], v[132:133], off offset:128
	global_load_dwordx4 v[40:43], v[98:99], off offset:128
	s_waitcnt vmcnt(1)
	v_pk_fma_f32 v[16:17], v[16:17], v[32:33], v[36:37]
	s_waitcnt vmcnt(0)
	v_pk_fma_f32 v[0:1], v[0:1], v[32:33], v[40:41]
	v_pk_fma_f32 v[2:3], v[2:3], v[34:35], v[42:43]
	global_store_dwordx4 v[98:99], v[0:3], off offset:128
	v_pk_fma_f32 v[18:19], v[18:19], v[34:35], v[38:39]
	global_store_dwordx4 v[132:133], v[16:19], off offset:128
	v_or_b32_e32 v0, 40, v134
	v_ashrrev_i32_e32 v1, 31, v0
	v_lshl_add_u64 v[0:1], v[0:1], 2, s[6:7]
	global_load_dwordx4 v[0:3], v[0:1], off
	global_load_dwordx4 v[16:19], v[132:133], off offset:160
	global_load_dwordx4 v[32:35], v[98:99], off offset:160
	s_waitcnt vmcnt(1)
	v_pk_fma_f32 v[16:17], v[20:21], v[0:1], v[16:17]
	s_waitcnt vmcnt(0)
	v_pk_fma_f32 v[0:1], v[4:5], v[0:1], v[32:33]
	v_pk_fma_f32 v[18:19], v[22:23], v[2:3], v[18:19]
	v_pk_fma_f32 v[2:3], v[6:7], v[2:3], v[34:35]
	global_store_dwordx4 v[98:99], v[0:3], off offset:160
	global_store_dwordx4 v[132:133], v[16:19], off offset:160
	s_nop 0
	v_or_b32_e32 v0, 48, v134
	v_ashrrev_i32_e32 v1, 31, v0
	v_lshl_add_u64 v[0:1], v[0:1], 2, s[6:7]
	global_load_dwordx4 v[0:3], v[0:1], off
	global_load_dwordx4 v[4:7], v[132:133], off offset:192
	global_load_dwordx4 v[16:19], v[98:99], off offset:192
	s_waitcnt vmcnt(1)
	v_pk_fma_f32 v[4:5], v[24:25], v[0:1], v[4:5]
	s_waitcnt vmcnt(0)
	v_pk_fma_f32 v[0:1], v[8:9], v[0:1], v[16:17]
	v_pk_fma_f32 v[6:7], v[26:27], v[2:3], v[6:7]
	v_pk_fma_f32 v[2:3], v[10:11], v[2:3], v[18:19]
	global_store_dwordx4 v[98:99], v[0:3], off offset:192
	global_store_dwordx4 v[132:133], v[4:7], off offset:192
	s_nop 0
	v_or_b32_e32 v0, 56, v134
	v_ashrrev_i32_e32 v1, 31, v0
	v_lshl_add_u64 v[0:1], v[0:1], 2, s[6:7]
	global_load_dwordx4 v[0:3], v[0:1], off
	global_load_dwordx4 v[4:7], v[132:133], off offset:224
	global_load_dwordx4 v[8:11], v[98:99], off offset:224
	s_waitcnt vmcnt(1)
	v_pk_fma_f32 v[4:5], v[28:29], v[0:1], v[4:5]
	s_waitcnt vmcnt(0)
	v_pk_fma_f32 v[0:1], v[12:13], v[0:1], v[8:9]
	v_pk_fma_f32 v[6:7], v[30:31], v[2:3], v[6:7]
	v_pk_fma_f32 v[2:3], v[14:15], v[2:3], v[10:11]
	global_store_dwordx4 v[132:133], v[4:7], off offset:224
	global_store_dwordx4 v[98:99], v[0:3], off offset:224
	s_cbranch_vccnz .LBB0_1243

.LBB0_1237:
	v_readlane_b32 s8, v248, 8
	v_readlane_b32 s9, v248, 9
	s_add_u32 s3, s8, s38
	s_addc_u32 s7, s9, s39
	s_and_b64 s[38:39], s[12:13], exec
	s_cselect_b32 s39, s7, 0
	s_cselect_b32 s38, s3, 0
	s_add_u32 s3, s62, s40
	s_addc_u32 s7, s63, s41
	s_and_b64 s[40:41], s[12:13], exec
	s_cselect_b32 s41, s7, 0
	s_cselect_b32 s40, s3, 0
	v_lshl_add_u64 v[4:5], s[38:39], 0, v[0:1]
	v_lshl_add_u64 v[0:1], s[40:41], 0, v[0:1]
	v_lshl_add_u64 v[146:147], v[0:1], 0, v[96:97]
	v_lshrrev_b32_e32 v0, 1, v2
	v_and_b32_e32 v1, 31, v2
	v_and_or_b32 v1, v0, s81, v1
	v_lshrrev_b32_e32 v0, 2, v2
	v_and_b32_e32 v0, 8, v0
	v_lshl_add_u64 v[148:149], v[4:5], 0, v[96:97]
	v_mad_u64_u32 v[4:5], s[38:39], v1, s84, v[0:1]
	v_and_b32_e32 v1, 0x5f, v2
	v_mad_u32_u24 v0, v1, s84, v0
	v_lshl_add_u32 v178, v4, 1, 0
	v_lshl_add_u32 v96, v0, 1, 0
	v_add_u32_e32 v179, 0xd800, v177
	s_setprio 1
	ds_read_b128 v[212:215], v96 offset:36864
	ds_read_b128 v[216:219], v178
	ds_read_b128 v[220:223], v178 offset:4608
	ds_read_b128 v[224:227], v96 offset:36896
	ds_read_b128 v[228:231], v178 offset:32
	ds_read_b128 v[244:247], v178 offset:4640
	ds_read_b128 v[252:255], v96 offset:41472
	s_waitcnt lgkmcnt(5)
	v_mfma_f32_32x32x16_bf16 v[32:47], v[212:215], v[216:219], 0
	s_waitcnt lgkmcnt(4)
	v_mfma_f32_32x32x16_bf16 v[48:63], v[212:215], v[220:223], 0
	ds_read_b128 v[212:215], v96 offset:41504
	s_waitcnt lgkmcnt(3)
	v_mfma_f32_32x32x16_bf16 v[32:47], v[224:227], v[228:231], v[32:47]
	s_waitcnt lgkmcnt(2)
	v_mfma_f32_32x32x16_bf16 v[48:63], v[224:227], v[244:247], v[48:63]
	ds_read_b128 v[224:227], v96 offset:36928
	s_waitcnt lgkmcnt(2)
	v_mfma_f32_32x32x16_bf16 v[16:31], v[252:255], v[216:219], 0
	ds_read_b128 v[216:219], v178 offset:64
	v_mfma_f32_32x32x16_bf16 v[0:15], v[252:255], v[220:223], 0
	ds_read_b128 v[252:255], v178 offset:4672
	ds_read_b128 v[220:223], v96 offset:41536
	s_waitcnt lgkmcnt(4)
	v_mfma_f32_32x32x16_bf16 v[16:31], v[212:215], v[228:231], v[16:31]
	ds_read_b128 v[228:231], v96 offset:36960
	v_mfma_f32_32x32x16_bf16 v[0:15], v[212:215], v[244:247], v[0:15]
	ds_read_b128 v[212:215], v178 offset:96
	ds_read_b128 v[244:247], v178 offset:4704
	s_waitcnt lgkmcnt(5)
	v_mfma_f32_32x32x16_bf16 v[32:47], v[224:227], v[216:219], v[32:47]
	s_mov_b32 s3, 0x10000
	v_add_co_u32_e32 v154, vcc, s3, v152
	s_mov_b32 s7, 0x20000
	s_nop 0
	v_addc_co_u32_e32 v155, vcc, 0, v153, vcc
	v_add_co_u32_e32 v156, vcc, s7, v152
	s_mov_b32 s8, 0x30000
	s_nop 0
	s_waitcnt lgkmcnt(4)
	v_mfma_f32_32x32x16_bf16 v[48:63], v[224:227], v[252:255], v[48:63]
	ds_read_b128 v[224:227], v96 offset:41568
	v_addc_co_u32_e32 v157, vcc, 0, v153, vcc
	v_add_co_u32_e32 v158, vcc, s8, v152
	s_waitcnt vmcnt(15)
	ds_write_b128 v177, v[100:103] offset:18432
	s_waitcnt vmcnt(14)
	ds_write_b128 v177, v[104:107] offset:23040
	s_waitcnt lgkmcnt(6)
	v_mfma_f32_32x32x16_bf16 v[16:31], v[220:223], v[216:219], v[16:31]
	s_waitcnt vmcnt(13)
	ds_write_b128 v177, v[108:111] offset:27648
	s_waitcnt vmcnt(12)
	ds_write_b128 v177, v[116:119] offset:32256
	v_mfma_f32_32x32x16_bf16 v[0:15], v[220:223], v[252:255], v[0:15]
	s_waitcnt vmcnt(11)
	ds_write_b128 v177, v[112:115] offset:55296
	s_waitcnt vmcnt(10)
	ds_write_b128 v177, v[120:123] offset:59904
	s_waitcnt vmcnt(9)
	ds_write_b128 v177, v[124:127] offset:64512
	s_waitcnt lgkmcnt(9)
	v_mfma_f32_32x32x16_bf16 v[32:47], v[228:231], v[212:215], v[32:47]
	s_waitcnt vmcnt(8)
	ds_write_b128 v179, v[128:131] offset:13824
	v_addc_co_u32_e32 v159, vcc, 0, v153, vcc
	v_add_co_u32_e32 v160, vcc, s3, v150
	s_waitcnt lgkmcnt(9)
	v_mfma_f32_32x32x16_bf16 v[48:63], v[228:231], v[244:247], v[48:63]
	global_load_dwordx4 v[98:101], v[152:153], off offset:384
	global_load_dwordx4 v[102:105], v[154:155], off offset:384
	v_addc_co_u32_e32 v161, vcc, 0, v151, vcc
	v_add_co_u32_e32 v170, vcc, s7, v150
	global_load_dwordx4 v[106:109], v[156:157], off offset:384
	s_waitcnt lgkmcnt(8)
	v_mfma_f32_32x32x16_bf16 v[16:31], v[224:227], v[212:215], v[16:31]
	s_nop 0
	v_addc_co_u32_e32 v171, vcc, 0, v151, vcc
	v_add_co_u32_e32 v172, vcc, s8, v150
	global_load_dwordx4 v[110:113], v[158:159], off offset:384
	global_load_dwordx4 v[114:117], v[150:151], off offset:384
	v_mfma_f32_32x32x16_bf16 v[0:15], v[224:227], v[244:247], v[0:15]
	v_addc_co_u32_e32 v173, vcc, 0, v151, vcc
	global_load_dwordx4 v[118:121], v[160:161], off offset:384
	global_load_dwordx4 v[122:125], v[170:171], off offset:384
	global_load_dwordx4 v[130:133], v[172:173], off offset:384
	s_setprio 0
	s_waitcnt lgkmcnt(0)
	s_barrier
	s_setprio 1
	ds_read_b128 v[212:215], v96 offset:55296
	ds_read_b128 v[216:219], v178 offset:18432
	ds_read_b128 v[220:223], v178 offset:23040
	ds_read_b128 v[224:227], v96 offset:59904
	ds_read_b128 v[228:231], v96 offset:55328
	ds_read_b128 v[244:247], v178 offset:18464
	ds_read_b128 v[252:255], v178 offset:23072
	s_waitcnt lgkmcnt(5)
	v_mfma_f32_32x32x16_bf16 v[32:47], v[212:215], v[216:219], v[32:47]
	s_waitcnt lgkmcnt(4)
	v_mfma_f32_32x32x16_bf16 v[48:63], v[212:215], v[220:223], v[48:63]
	ds_read_b128 v[212:215], v96 offset:59936
	s_waitcnt lgkmcnt(4)
	v_mfma_f32_32x32x16_bf16 v[16:31], v[224:227], v[216:219], v[16:31]
	ds_read_b128 v[216:219], v96 offset:55360
	v_mfma_f32_32x32x16_bf16 v[0:15], v[224:227], v[220:223], v[0:15]
	ds_read_b128 v[224:227], v178 offset:18496
	ds_read_b128 v[220:223], v178 offset:23104
	s_waitcnt lgkmcnt(5)
	v_mfma_f32_32x32x16_bf16 v[32:47], v[228:231], v[244:247], v[32:47]
	s_waitcnt lgkmcnt(4)
	v_mfma_f32_32x32x16_bf16 v[48:63], v[228:231], v[252:255], v[48:63]
	ds_read_b128 v[228:231], v96 offset:59968
	s_waitcnt lgkmcnt(4)
	v_mfma_f32_32x32x16_bf16 v[16:31], v[212:215], v[244:247], v[16:31]
	ds_read_b128 v[244:247], v96 offset:55392
	v_mfma_f32_32x32x16_bf16 v[0:15], v[212:215], v[252:255], v[0:15]
	ds_read_b128 v[212:215], v178 offset:18528
	ds_read_b128 v[252:255], v178 offset:23136
	s_waitcnt lgkmcnt(5)
	v_mfma_f32_32x32x16_bf16 v[32:47], v[216:219], v[224:227], v[32:47]
	s_waitcnt vmcnt(15)
	ds_write_b128 v177, v[64:67]
	global_load_dwordx4 v[64:67], v[152:153], off offset:512
	s_waitcnt lgkmcnt(5)
	v_mfma_f32_32x32x16_bf16 v[48:63], v[216:219], v[220:223], v[48:63]
	ds_read_b128 v[216:219], v96 offset:60000
	s_waitcnt vmcnt(15)
	ds_write_b128 v177, v[68:71] offset:4608
	s_waitcnt vmcnt(14)
	ds_write_b128 v177, v[72:75] offset:9216
	s_waitcnt lgkmcnt(7)
	v_mfma_f32_32x32x16_bf16 v[16:31], v[228:231], v[224:227], v[16:31]
	global_load_dwordx4 v[72:75], v[154:155], off offset:512
	s_waitcnt vmcnt(14)
	ds_write_b128 v177, v[76:79] offset:13824
	v_mfma_f32_32x32x16_bf16 v[0:15], v[228:231], v[220:223], v[0:15]
	global_load_dwordx4 v[76:79], v[156:157], off offset:512
	s_waitcnt vmcnt(14)
	ds_write_b128 v177, v[80:83] offset:36864
	s_waitcnt lgkmcnt(7)
	v_mfma_f32_32x32x16_bf16 v[32:47], v[244:247], v[212:215], v[32:47]
	global_load_dwordx4 v[80:83], v[158:159], off offset:512
	global_load_dwordx4 v[126:129], v[150:151], off offset:512
	s_waitcnt lgkmcnt(6)
	v_mfma_f32_32x32x16_bf16 v[48:63], v[244:247], v[252:255], v[48:63]
	s_waitcnt vmcnt(15)
	ds_write_b128 v177, v[84:87] offset:41472
	global_load_dwordx4 v[134:137], v[160:161], off offset:512
	s_waitcnt lgkmcnt(5)
	v_mfma_f32_32x32x16_bf16 v[16:31], v[216:219], v[212:215], v[16:31]
	s_waitcnt vmcnt(15)
	ds_write_b128 v177, v[88:91] offset:46080
	global_load_dwordx4 v[138:141], v[170:171], off offset:512
	v_mfma_f32_32x32x16_bf16 v[0:15], v[216:219], v[252:255], v[0:15]
	s_waitcnt vmcnt(15)
	ds_write_b128 v177, v[92:95] offset:50688
	global_load_dwordx4 v[142:145], v[172:173], off offset:512
	s_setprio 0
	s_waitcnt lgkmcnt(0)
	s_barrier
	s_setprio 1
	ds_read_b128 v[212:215], v96 offset:36864
	ds_read_b128 v[216:219], v178
	ds_read_b128 v[220:223], v178 offset:4608
	ds_read_b128 v[224:227], v96 offset:41472
	ds_read_b128 v[228:231], v96 offset:36896
	ds_read_b128 v[244:247], v178 offset:32
	ds_read_b128 v[252:255], v178 offset:4640
	s_waitcnt lgkmcnt(5)
	v_mfma_f32_32x32x16_bf16 v[32:47], v[212:215], v[216:219], v[32:47]
	s_waitcnt lgkmcnt(4)
	v_mfma_f32_32x32x16_bf16 v[48:63], v[212:215], v[220:223], v[48:63]
	ds_read_b128 v[212:215], v96 offset:41504
	s_waitcnt lgkmcnt(4)
	v_mfma_f32_32x32x16_bf16 v[16:31], v[224:227], v[216:219], v[16:31]
	ds_read_b128 v[216:219], v96 offset:36928
	v_mfma_f32_32x32x16_bf16 v[0:15], v[224:227], v[220:223], v[0:15]
	ds_read_b128 v[224:227], v178 offset:64
	ds_read_b128 v[220:223], v178 offset:4672
	s_waitcnt lgkmcnt(5)
	v_mfma_f32_32x32x16_bf16 v[32:47], v[228:231], v[244:247], v[32:47]
	s_waitcnt lgkmcnt(4)
	v_mfma_f32_32x32x16_bf16 v[48:63], v[228:231], v[252:255], v[48:63]
	ds_read_b128 v[228:231], v96 offset:41536
	s_waitcnt lgkmcnt(4)
	v_mfma_f32_32x32x16_bf16 v[16:31], v[212:215], v[244:247], v[16:31]
	ds_read_b128 v[244:247], v96 offset:36960
	v_mfma_f32_32x32x16_bf16 v[0:15], v[212:215], v[252:255], v[0:15]
	ds_read_b128 v[212:215], v178 offset:96
	ds_read_b128 v[252:255], v178 offset:4704
	s_waitcnt lgkmcnt(5)
	v_mfma_f32_32x32x16_bf16 v[32:47], v[216:219], v[224:227], v[32:47]
	s_waitcnt vmcnt(15)
	ds_write_b128 v177, v[98:101] offset:18432
	global_load_dwordx4 v[68:71], v[152:153], off offset:640
	s_waitcnt lgkmcnt(5)
	v_mfma_f32_32x32x16_bf16 v[48:63], v[216:219], v[220:223], v[48:63]
	ds_read_b128 v[216:219], v96 offset:41568
	s_waitcnt vmcnt(15)
	ds_write_b128 v177, v[102:105] offset:23040
	global_load_dwordx4 v[84:87], v[154:155], off offset:640
	s_waitcnt lgkmcnt(6)
	v_mfma_f32_32x32x16_bf16 v[16:31], v[228:231], v[224:227], v[16:31]
	s_waitcnt vmcnt(15)
	ds_write_b128 v177, v[106:109] offset:27648
	global_load_dwordx4 v[88:91], v[156:157], off offset:640
	v_mfma_f32_32x32x16_bf16 v[0:15], v[228:231], v[220:223], v[0:15]
	s_waitcnt vmcnt(15)
	ds_write_b128 v177, v[110:113] offset:32256
	global_load_dwordx4 v[92:95], v[158:159], off offset:640
	s_waitcnt lgkmcnt(6)
	v_mfma_f32_32x32x16_bf16 v[32:47], v[244:247], v[212:215], v[32:47]
	s_waitcnt vmcnt(15)
	ds_write_b128 v177, v[114:117] offset:55296
	global_load_dwordx4 v[98:101], v[150:151], off offset:640
	s_waitcnt lgkmcnt(6)
	v_mfma_f32_32x32x16_bf16 v[48:63], v[244:247], v[252:255], v[48:63]
	s_waitcnt vmcnt(15)
	ds_write_b128 v177, v[118:121] offset:59904
	global_load_dwordx4 v[106:109], v[160:161], off offset:640
	s_waitcnt lgkmcnt(5)
	v_mfma_f32_32x32x16_bf16 v[16:31], v[216:219], v[212:215], v[16:31]
	s_waitcnt vmcnt(15)
	ds_write_b128 v177, v[122:125] offset:64512
	global_load_dwordx4 v[110:113], v[170:171], off offset:640
	v_mfma_f32_32x32x16_bf16 v[0:15], v[216:219], v[252:255], v[0:15]
	s_waitcnt vmcnt(15)
	ds_write_b128 v179, v[130:133] offset:13824
	global_load_dwordx4 v[114:117], v[172:173], off offset:640
	s_setprio 0
	s_waitcnt lgkmcnt(0)
	s_barrier
	s_setprio 1
	ds_read_b128 v[212:215], v96 offset:55296
	ds_read_b128 v[216:219], v178 offset:18432
	ds_read_b128 v[220:223], v178 offset:23040
	ds_read_b128 v[224:227], v96 offset:59904
	ds_read_b128 v[228:231], v96 offset:55328
	ds_read_b128 v[244:247], v178 offset:18464
	ds_read_b128 v[252:255], v178 offset:23072
	s_waitcnt lgkmcnt(5)
	v_mfma_f32_32x32x16_bf16 v[32:47], v[212:215], v[216:219], v[32:47]
	s_waitcnt lgkmcnt(4)
	v_mfma_f32_32x32x16_bf16 v[48:63], v[212:215], v[220:223], v[48:63]
	ds_read_b128 v[212:215], v96 offset:59936
	s_waitcnt lgkmcnt(4)
	v_mfma_f32_32x32x16_bf16 v[16:31], v[224:227], v[216:219], v[16:31]
	ds_read_b128 v[216:219], v96 offset:55360
	v_mfma_f32_32x32x16_bf16 v[0:15], v[224:227], v[220:223], v[0:15]
	ds_read_b128 v[224:227], v178 offset:18496
	ds_read_b128 v[220:223], v178 offset:23104
	s_waitcnt lgkmcnt(5)
	v_mfma_f32_32x32x16_bf16 v[32:47], v[228:231], v[244:247], v[32:47]
	s_waitcnt lgkmcnt(4)
	v_mfma_f32_32x32x16_bf16 v[48:63], v[228:231], v[252:255], v[48:63]
	ds_read_b128 v[228:231], v96 offset:59968
	s_waitcnt lgkmcnt(4)
	v_mfma_f32_32x32x16_bf16 v[16:31], v[212:215], v[244:247], v[16:31]
	ds_read_b128 v[244:247], v96 offset:55392
	v_mfma_f32_32x32x16_bf16 v[0:15], v[212:215], v[252:255], v[0:15]
	ds_read_b128 v[212:215], v178 offset:18528
	ds_read_b128 v[252:255], v178 offset:23136
	s_waitcnt lgkmcnt(5)
	v_mfma_f32_32x32x16_bf16 v[32:47], v[216:219], v[224:227], v[32:47]
	s_waitcnt vmcnt(15)
	ds_write_b128 v177, v[64:67]
	global_load_dwordx4 v[64:67], v[152:153], off offset:768
	s_waitcnt lgkmcnt(5)
	v_mfma_f32_32x32x16_bf16 v[48:63], v[216:219], v[220:223], v[48:63]
	ds_read_b128 v[216:219], v96 offset:60000
	s_waitcnt vmcnt(15)
	ds_write_b128 v177, v[72:75] offset:4608
	global_load_dwordx4 v[72:75], v[154:155], off offset:768
	s_waitcnt lgkmcnt(6)
	v_mfma_f32_32x32x16_bf16 v[16:31], v[228:231], v[224:227], v[16:31]
	s_waitcnt vmcnt(15)
	ds_write_b128 v177, v[76:79] offset:9216
	global_load_dwordx4 v[76:79], v[156:157], off offset:768
	v_mfma_f32_32x32x16_bf16 v[0:15], v[228:231], v[220:223], v[0:15]
	s_waitcnt vmcnt(15)
	ds_write_b128 v177, v[80:83] offset:13824
	global_load_dwordx4 v[80:83], v[158:159], off offset:768
	s_waitcnt lgkmcnt(6)
	v_mfma_f32_32x32x16_bf16 v[32:47], v[244:247], v[212:215], v[32:47]
	s_waitcnt vmcnt(15)
	ds_write_b128 v177, v[126:129] offset:36864
	global_load_dwordx4 v[102:105], v[150:151], off offset:768
	s_waitcnt lgkmcnt(6)
	v_mfma_f32_32x32x16_bf16 v[48:63], v[244:247], v[252:255], v[48:63]
	s_waitcnt vmcnt(15)
	ds_write_b128 v177, v[134:137] offset:41472
	global_load_dwordx4 v[118:121], v[160:161], off offset:768
	s_waitcnt lgkmcnt(5)
	v_mfma_f32_32x32x16_bf16 v[16:31], v[216:219], v[212:215], v[16:31]
	s_waitcnt vmcnt(15)
	ds_write_b128 v177, v[138:141] offset:46080
	global_load_dwordx4 v[122:125], v[170:171], off offset:768
	v_mfma_f32_32x32x16_bf16 v[0:15], v[216:219], v[252:255], v[0:15]
	s_waitcnt vmcnt(15)
	ds_write_b128 v177, v[142:145] offset:50688
	global_load_dwordx4 v[126:129], v[172:173], off offset:768
	s_setprio 0
	s_waitcnt lgkmcnt(0)
	s_barrier
	s_setprio 1
	ds_read_b128 v[212:215], v96 offset:36864
	ds_read_b128 v[216:219], v178
	ds_read_b128 v[220:223], v178 offset:4608
	ds_read_b128 v[224:227], v96 offset:41472
	ds_read_b128 v[228:231], v96 offset:36896
	ds_read_b128 v[244:247], v178 offset:32
	ds_read_b128 v[252:255], v178 offset:4640
	s_waitcnt lgkmcnt(5)
	v_mfma_f32_32x32x16_bf16 v[32:47], v[212:215], v[216:219], v[32:47]
	s_waitcnt lgkmcnt(4)
	v_mfma_f32_32x32x16_bf16 v[48:63], v[212:215], v[220:223], v[48:63]
	ds_read_b128 v[212:215], v96 offset:41504
	s_waitcnt lgkmcnt(4)
	v_mfma_f32_32x32x16_bf16 v[16:31], v[224:227], v[216:219], v[16:31]
	ds_read_b128 v[216:219], v96 offset:36928
	v_mfma_f32_32x32x16_bf16 v[0:15], v[224:227], v[220:223], v[0:15]
	ds_read_b128 v[224:227], v178 offset:64
	ds_read_b128 v[220:223], v178 offset:4672
	s_waitcnt lgkmcnt(5)
	v_mfma_f32_32x32x16_bf16 v[32:47], v[228:231], v[244:247], v[32:47]
	s_waitcnt lgkmcnt(4)
	v_mfma_f32_32x32x16_bf16 v[48:63], v[228:231], v[252:255], v[48:63]
	ds_read_b128 v[228:231], v96 offset:41536
	s_waitcnt lgkmcnt(4)
	v_mfma_f32_32x32x16_bf16 v[16:31], v[212:215], v[244:247], v[16:31]
	ds_read_b128 v[244:247], v96 offset:36960
	v_mfma_f32_32x32x16_bf16 v[0:15], v[212:215], v[252:255], v[0:15]
	ds_read_b128 v[212:215], v178 offset:96
	ds_read_b128 v[252:255], v178 offset:4704
	s_waitcnt lgkmcnt(5)
	v_mfma_f32_32x32x16_bf16 v[32:47], v[216:219], v[224:227], v[32:47]
	s_waitcnt vmcnt(15)
	ds_write_b128 v177, v[68:71] offset:18432
	global_load_dwordx4 v[68:71], v[152:153], off offset:896
	s_waitcnt lgkmcnt(5)
	v_mfma_f32_32x32x16_bf16 v[48:63], v[216:219], v[220:223], v[48:63]
	ds_read_b128 v[216:219], v96 offset:41568
	s_waitcnt vmcnt(15)
	ds_write_b128 v177, v[84:87] offset:23040
	global_load_dwordx4 v[84:87], v[154:155], off offset:896
	s_waitcnt lgkmcnt(6)
	v_mfma_f32_32x32x16_bf16 v[16:31], v[228:231], v[224:227], v[16:31]
	s_waitcnt vmcnt(15)
	ds_write_b128 v177, v[88:91] offset:27648
	global_load_dwordx4 v[88:91], v[156:157], off offset:896
	v_mfma_f32_32x32x16_bf16 v[0:15], v[228:231], v[220:223], v[0:15]
	s_waitcnt vmcnt(15)
	ds_write_b128 v177, v[92:95] offset:32256
	global_load_dwordx4 v[92:95], v[158:159], off offset:896
	s_waitcnt lgkmcnt(6)
	v_mfma_f32_32x32x16_bf16 v[32:47], v[244:247], v[212:215], v[32:47]
	s_waitcnt vmcnt(15)
	ds_write_b128 v177, v[98:101] offset:55296
	global_load_dwordx4 v[98:101], v[150:151], off offset:896
	s_waitcnt lgkmcnt(6)
	v_mfma_f32_32x32x16_bf16 v[48:63], v[244:247], v[252:255], v[48:63]
	s_waitcnt vmcnt(15)
	ds_write_b128 v177, v[106:109] offset:59904
	global_load_dwordx4 v[106:109], v[160:161], off offset:896
	s_waitcnt lgkmcnt(5)
	v_mfma_f32_32x32x16_bf16 v[16:31], v[216:219], v[212:215], v[16:31]
	s_waitcnt vmcnt(15)
	ds_write_b128 v177, v[110:113] offset:64512
	global_load_dwordx4 v[110:113], v[170:171], off offset:896
	v_mfma_f32_32x32x16_bf16 v[0:15], v[216:219], v[252:255], v[0:15]
	s_waitcnt vmcnt(15)
	ds_write_b128 v179, v[114:117] offset:13824
	global_load_dwordx4 v[114:117], v[172:173], off offset:896
	s_setprio 0
	s_waitcnt lgkmcnt(0)
	s_barrier
	s_setprio 1
	ds_read_b128 v[212:215], v96 offset:55296
	ds_read_b128 v[216:219], v178 offset:18432
	ds_read_b128 v[220:223], v178 offset:23040
	ds_read_b128 v[224:227], v96 offset:59904
	ds_read_b128 v[228:231], v96 offset:55328
	ds_read_b128 v[244:247], v178 offset:18464
	ds_read_b128 v[252:255], v178 offset:23072
	s_waitcnt lgkmcnt(5)
	v_mfma_f32_32x32x16_bf16 v[32:47], v[212:215], v[216:219], v[32:47]
	s_waitcnt lgkmcnt(4)
	v_mfma_f32_32x32x16_bf16 v[48:63], v[212:215], v[220:223], v[48:63]
	ds_read_b128 v[212:215], v96 offset:59936
	s_waitcnt lgkmcnt(4)
	v_mfma_f32_32x32x16_bf16 v[16:31], v[224:227], v[216:219], v[16:31]
	ds_read_b128 v[216:219], v96 offset:55360
	v_mfma_f32_32x32x16_bf16 v[0:15], v[224:227], v[220:223], v[0:15]
	ds_read_b128 v[224:227], v178 offset:18496
	ds_read_b128 v[220:223], v178 offset:23104
	s_waitcnt lgkmcnt(5)
	v_mfma_f32_32x32x16_bf16 v[32:47], v[228:231], v[244:247], v[32:47]
	s_waitcnt lgkmcnt(4)
	v_mfma_f32_32x32x16_bf16 v[48:63], v[228:231], v[252:255], v[48:63]
	ds_read_b128 v[228:231], v96 offset:59968
	s_waitcnt lgkmcnt(4)
	v_mfma_f32_32x32x16_bf16 v[16:31], v[212:215], v[244:247], v[16:31]
	ds_read_b128 v[244:247], v96 offset:55392
	v_mfma_f32_32x32x16_bf16 v[0:15], v[212:215], v[252:255], v[0:15]
	ds_read_b128 v[212:215], v178 offset:18528
	ds_read_b128 v[252:255], v178 offset:23136
	s_waitcnt lgkmcnt(5)
	v_mfma_f32_32x32x16_bf16 v[32:47], v[216:219], v[224:227], v[32:47]
	s_waitcnt vmcnt(15)
	ds_write_b128 v177, v[64:67]
	global_load_dwordx4 v[64:67], v[152:153], off offset:1024
	s_waitcnt lgkmcnt(5)
	v_mfma_f32_32x32x16_bf16 v[48:63], v[216:219], v[220:223], v[48:63]
	ds_read_b128 v[216:219], v96 offset:60000
	s_waitcnt vmcnt(15)
	ds_write_b128 v177, v[72:75] offset:4608
	global_load_dwordx4 v[72:75], v[154:155], off offset:1024
	s_waitcnt lgkmcnt(6)
	v_mfma_f32_32x32x16_bf16 v[16:31], v[228:231], v[224:227], v[16:31]
	s_waitcnt vmcnt(15)
	ds_write_b128 v177, v[76:79] offset:9216
	global_load_dwordx4 v[76:79], v[156:157], off offset:1024
	v_mfma_f32_32x32x16_bf16 v[0:15], v[228:231], v[220:223], v[0:15]
	s_waitcnt vmcnt(15)
	ds_write_b128 v177, v[80:83] offset:13824
	global_load_dwordx4 v[80:83], v[158:159], off offset:1024
	s_waitcnt lgkmcnt(6)
	v_mfma_f32_32x32x16_bf16 v[32:47], v[244:247], v[212:215], v[32:47]
	s_waitcnt vmcnt(15)
	ds_write_b128 v177, v[102:105] offset:36864
	global_load_dwordx4 v[102:105], v[150:151], off offset:1024
	s_waitcnt lgkmcnt(6)
	v_mfma_f32_32x32x16_bf16 v[48:63], v[244:247], v[252:255], v[48:63]
	s_waitcnt vmcnt(15)
	ds_write_b128 v177, v[118:121] offset:41472
	global_load_dwordx4 v[118:121], v[160:161], off offset:1024
	s_waitcnt lgkmcnt(5)
	v_mfma_f32_32x32x16_bf16 v[16:31], v[216:219], v[212:215], v[16:31]
	s_waitcnt vmcnt(15)
	ds_write_b128 v177, v[122:125] offset:46080
	global_load_dwordx4 v[122:125], v[170:171], off offset:1024
	v_mfma_f32_32x32x16_bf16 v[0:15], v[216:219], v[252:255], v[0:15]
	s_waitcnt vmcnt(15)
	ds_write_b128 v177, v[126:129] offset:50688
	global_load_dwordx4 v[126:129], v[172:173], off offset:1024
	s_setprio 0
	s_waitcnt lgkmcnt(0)
	s_barrier
	s_setprio 1
	ds_read_b128 v[212:215], v96 offset:36864
	ds_read_b128 v[216:219], v178
	ds_read_b128 v[220:223], v178 offset:4608
	ds_read_b128 v[224:227], v96 offset:41472
	ds_read_b128 v[228:231], v96 offset:36896
	ds_read_b128 v[244:247], v178 offset:32
	ds_read_b128 v[252:255], v178 offset:4640
	s_waitcnt lgkmcnt(5)
	v_mfma_f32_32x32x16_bf16 v[32:47], v[212:215], v[216:219], v[32:47]
	s_waitcnt lgkmcnt(4)
	v_mfma_f32_32x32x16_bf16 v[48:63], v[212:215], v[220:223], v[48:63]
	ds_read_b128 v[212:215], v96 offset:41504
	s_waitcnt lgkmcnt(4)
	v_mfma_f32_32x32x16_bf16 v[16:31], v[224:227], v[216:219], v[16:31]
	ds_read_b128 v[216:219], v96 offset:36928
	v_mfma_f32_32x32x16_bf16 v[0:15], v[224:227], v[220:223], v[0:15]
	ds_read_b128 v[224:227], v178 offset:64
	ds_read_b128 v[220:223], v178 offset:4672
	s_waitcnt lgkmcnt(5)
	v_mfma_f32_32x32x16_bf16 v[32:47], v[228:231], v[244:247], v[32:47]
	s_waitcnt lgkmcnt(4)
	v_mfma_f32_32x32x16_bf16 v[48:63], v[228:231], v[252:255], v[48:63]
	ds_read_b128 v[228:231], v96 offset:41536
	s_waitcnt lgkmcnt(4)
	v_mfma_f32_32x32x16_bf16 v[16:31], v[212:215], v[244:247], v[16:31]
	ds_read_b128 v[244:247], v96 offset:36960
	v_mfma_f32_32x32x16_bf16 v[0:15], v[212:215], v[252:255], v[0:15]
	ds_read_b128 v[212:215], v178 offset:96
	ds_read_b128 v[252:255], v178 offset:4704
	s_waitcnt lgkmcnt(5)
	v_mfma_f32_32x32x16_bf16 v[32:47], v[216:219], v[224:227], v[32:47]
	s_waitcnt vmcnt(15)
	ds_write_b128 v177, v[68:71] offset:18432
	global_load_dwordx4 v[68:71], v[152:153], off offset:1152
	s_waitcnt lgkmcnt(5)
	v_mfma_f32_32x32x16_bf16 v[48:63], v[216:219], v[220:223], v[48:63]
	ds_read_b128 v[216:219], v96 offset:41568
	s_waitcnt vmcnt(15)
	ds_write_b128 v177, v[84:87] offset:23040
	global_load_dwordx4 v[84:87], v[154:155], off offset:1152
	s_waitcnt lgkmcnt(6)
	v_mfma_f32_32x32x16_bf16 v[16:31], v[228:231], v[224:227], v[16:31]
	s_waitcnt vmcnt(15)
	ds_write_b128 v177, v[88:91] offset:27648
	global_load_dwordx4 v[88:91], v[156:157], off offset:1152
	v_mfma_f32_32x32x16_bf16 v[0:15], v[228:231], v[220:223], v[0:15]
	s_waitcnt vmcnt(15)
	ds_write_b128 v177, v[92:95] offset:32256
	global_load_dwordx4 v[92:95], v[158:159], off offset:1152
	s_waitcnt lgkmcnt(6)
	v_mfma_f32_32x32x16_bf16 v[32:47], v[244:247], v[212:215], v[32:47]
	s_waitcnt vmcnt(15)
	ds_write_b128 v177, v[98:101] offset:55296
	global_load_dwordx4 v[98:101], v[150:151], off offset:1152
	s_waitcnt lgkmcnt(6)
	v_mfma_f32_32x32x16_bf16 v[48:63], v[244:247], v[252:255], v[48:63]
	s_waitcnt vmcnt(15)
	ds_write_b128 v177, v[106:109] offset:59904
	global_load_dwordx4 v[106:109], v[160:161], off offset:1152
	s_waitcnt lgkmcnt(5)
	v_mfma_f32_32x32x16_bf16 v[16:31], v[216:219], v[212:215], v[16:31]
	s_waitcnt vmcnt(15)
	ds_write_b128 v177, v[110:113] offset:64512
	global_load_dwordx4 v[110:113], v[170:171], off offset:1152
	v_mfma_f32_32x32x16_bf16 v[0:15], v[216:219], v[252:255], v[0:15]
	s_waitcnt vmcnt(15)
	ds_write_b128 v179, v[114:117] offset:13824
	global_load_dwordx4 v[114:117], v[172:173], off offset:1152
	s_setprio 0
	s_waitcnt lgkmcnt(0)
	s_barrier
	s_setprio 1
	ds_read_b128 v[212:215], v96 offset:55296
	ds_read_b128 v[216:219], v178 offset:18432
	ds_read_b128 v[220:223], v178 offset:23040
	ds_read_b128 v[224:227], v96 offset:59904
	ds_read_b128 v[228:231], v96 offset:55328
	ds_read_b128 v[244:247], v178 offset:18464
	ds_read_b128 v[252:255], v178 offset:23072
	s_waitcnt lgkmcnt(5)
	v_mfma_f32_32x32x16_bf16 v[32:47], v[212:215], v[216:219], v[32:47]
	s_waitcnt lgkmcnt(4)
	v_mfma_f32_32x32x16_bf16 v[48:63], v[212:215], v[220:223], v[48:63]
	ds_read_b128 v[212:215], v96 offset:59936
	s_waitcnt lgkmcnt(4)
	v_mfma_f32_32x32x16_bf16 v[16:31], v[224:227], v[216:219], v[16:31]
	ds_read_b128 v[216:219], v96 offset:55360
	v_mfma_f32_32x32x16_bf16 v[0:15], v[224:227], v[220:223], v[0:15]
	ds_read_b128 v[224:227], v178 offset:18496
	ds_read_b128 v[220:223], v178 offset:23104
	s_waitcnt lgkmcnt(5)
	v_mfma_f32_32x32x16_bf16 v[32:47], v[228:231], v[244:247], v[32:47]
	s_waitcnt lgkmcnt(4)
	v_mfma_f32_32x32x16_bf16 v[48:63], v[228:231], v[252:255], v[48:63]
	ds_read_b128 v[228:231], v96 offset:59968
	s_waitcnt lgkmcnt(4)
	v_mfma_f32_32x32x16_bf16 v[16:31], v[212:215], v[244:247], v[16:31]
	ds_read_b128 v[244:247], v96 offset:55392
	v_mfma_f32_32x32x16_bf16 v[0:15], v[212:215], v[252:255], v[0:15]
	ds_read_b128 v[212:215], v178 offset:18528
	ds_read_b128 v[252:255], v178 offset:23136
	s_waitcnt lgkmcnt(5)
	v_mfma_f32_32x32x16_bf16 v[32:47], v[216:219], v[224:227], v[32:47]
	s_waitcnt vmcnt(15)
	ds_write_b128 v177, v[64:67]
	global_load_dwordx4 v[64:67], v[152:153], off offset:1280
	s_waitcnt lgkmcnt(5)
	v_mfma_f32_32x32x16_bf16 v[48:63], v[216:219], v[220:223], v[48:63]
	ds_read_b128 v[216:219], v96 offset:60000
	s_waitcnt vmcnt(15)
	ds_write_b128 v177, v[72:75] offset:4608
	global_load_dwordx4 v[72:75], v[154:155], off offset:1280
	s_waitcnt lgkmcnt(6)
	v_mfma_f32_32x32x16_bf16 v[16:31], v[228:231], v[224:227], v[16:31]
	s_waitcnt vmcnt(15)
	ds_write_b128 v177, v[76:79] offset:9216
	global_load_dwordx4 v[76:79], v[156:157], off offset:1280
	v_mfma_f32_32x32x16_bf16 v[0:15], v[228:231], v[220:223], v[0:15]
	s_waitcnt vmcnt(15)
	ds_write_b128 v177, v[80:83] offset:13824
	global_load_dwordx4 v[80:83], v[158:159], off offset:1280
	s_waitcnt lgkmcnt(6)
	v_mfma_f32_32x32x16_bf16 v[32:47], v[244:247], v[212:215], v[32:47]
	s_waitcnt vmcnt(15)
	ds_write_b128 v177, v[102:105] offset:36864
	global_load_dwordx4 v[102:105], v[150:151], off offset:1280
	s_waitcnt lgkmcnt(6)
	v_mfma_f32_32x32x16_bf16 v[48:63], v[244:247], v[252:255], v[48:63]
	s_waitcnt vmcnt(15)
	ds_write_b128 v177, v[118:121] offset:41472
	global_load_dwordx4 v[118:121], v[160:161], off offset:1280
	s_waitcnt lgkmcnt(5)
	v_mfma_f32_32x32x16_bf16 v[16:31], v[216:219], v[212:215], v[16:31]
	s_waitcnt vmcnt(15)
	ds_write_b128 v177, v[122:125] offset:46080
	global_load_dwordx4 v[122:125], v[170:171], off offset:1280
	v_mfma_f32_32x32x16_bf16 v[0:15], v[216:219], v[252:255], v[0:15]
	s_waitcnt vmcnt(15)
	ds_write_b128 v177, v[126:129] offset:50688
	global_load_dwordx4 v[126:129], v[172:173], off offset:1280
	s_setprio 0
	s_waitcnt lgkmcnt(0)
	s_barrier
	s_setprio 1
	ds_read_b128 v[212:215], v96 offset:36864
	ds_read_b128 v[216:219], v178
	ds_read_b128 v[220:223], v178 offset:4608
	ds_read_b128 v[224:227], v96 offset:41472
	ds_read_b128 v[228:231], v96 offset:36896
	ds_read_b128 v[244:247], v178 offset:32
	ds_read_b128 v[252:255], v178 offset:4640
	s_waitcnt lgkmcnt(5)
	v_mfma_f32_32x32x16_bf16 v[32:47], v[212:215], v[216:219], v[32:47]
	s_waitcnt lgkmcnt(4)
	v_mfma_f32_32x32x16_bf16 v[48:63], v[212:215], v[220:223], v[48:63]
	ds_read_b128 v[212:215], v96 offset:41504
	s_waitcnt lgkmcnt(4)
	v_mfma_f32_32x32x16_bf16 v[16:31], v[224:227], v[216:219], v[16:31]
	ds_read_b128 v[216:219], v96 offset:36928
	v_mfma_f32_32x32x16_bf16 v[0:15], v[224:227], v[220:223], v[0:15]
	ds_read_b128 v[224:227], v178 offset:64
	ds_read_b128 v[220:223], v178 offset:4672
	s_waitcnt lgkmcnt(5)
	v_mfma_f32_32x32x16_bf16 v[32:47], v[228:231], v[244:247], v[32:47]
	s_waitcnt lgkmcnt(4)
	v_mfma_f32_32x32x16_bf16 v[48:63], v[228:231], v[252:255], v[48:63]
	ds_read_b128 v[228:231], v96 offset:41536
	s_waitcnt lgkmcnt(4)
	v_mfma_f32_32x32x16_bf16 v[16:31], v[212:215], v[244:247], v[16:31]
	ds_read_b128 v[244:247], v96 offset:36960
	v_mfma_f32_32x32x16_bf16 v[0:15], v[212:215], v[252:255], v[0:15]
	ds_read_b128 v[212:215], v178 offset:96
	ds_read_b128 v[252:255], v178 offset:4704
	s_waitcnt lgkmcnt(5)
	v_mfma_f32_32x32x16_bf16 v[32:47], v[216:219], v[224:227], v[32:47]
	s_waitcnt vmcnt(15)
	ds_write_b128 v177, v[68:71] offset:18432
	global_load_dwordx4 v[68:71], v[152:153], off offset:1408
	s_waitcnt lgkmcnt(5)
	v_mfma_f32_32x32x16_bf16 v[48:63], v[216:219], v[220:223], v[48:63]
	ds_read_b128 v[216:219], v96 offset:41568
	s_waitcnt vmcnt(15)
	ds_write_b128 v177, v[84:87] offset:23040
	global_load_dwordx4 v[84:87], v[154:155], off offset:1408
	s_waitcnt lgkmcnt(6)
	v_mfma_f32_32x32x16_bf16 v[16:31], v[228:231], v[224:227], v[16:31]
	s_waitcnt vmcnt(15)
	ds_write_b128 v177, v[88:91] offset:27648
	global_load_dwordx4 v[88:91], v[156:157], off offset:1408
	v_mfma_f32_32x32x16_bf16 v[0:15], v[228:231], v[220:223], v[0:15]
	s_waitcnt vmcnt(15)
	ds_write_b128 v177, v[92:95] offset:32256
	global_load_dwordx4 v[92:95], v[158:159], off offset:1408
	s_waitcnt lgkmcnt(6)
	v_mfma_f32_32x32x16_bf16 v[32:47], v[244:247], v[212:215], v[32:47]
	s_waitcnt vmcnt(15)
	ds_write_b128 v177, v[98:101] offset:55296
	global_load_dwordx4 v[98:101], v[150:151], off offset:1408
	s_waitcnt lgkmcnt(6)
	v_mfma_f32_32x32x16_bf16 v[48:63], v[244:247], v[252:255], v[48:63]
	s_waitcnt vmcnt(15)
	ds_write_b128 v177, v[106:109] offset:59904
	global_load_dwordx4 v[106:109], v[160:161], off offset:1408
	s_waitcnt lgkmcnt(5)
	v_mfma_f32_32x32x16_bf16 v[16:31], v[216:219], v[212:215], v[16:31]
	s_waitcnt vmcnt(15)
	ds_write_b128 v177, v[110:113] offset:64512
	global_load_dwordx4 v[110:113], v[170:171], off offset:1408
	v_mfma_f32_32x32x16_bf16 v[0:15], v[216:219], v[252:255], v[0:15]
	s_waitcnt vmcnt(15)
	ds_write_b128 v179, v[114:117] offset:13824
	global_load_dwordx4 v[130:133], v[172:173], off offset:1408
	s_setprio 0
	s_waitcnt lgkmcnt(0)
	s_barrier
	s_setprio 1
	ds_read_b128 v[212:215], v96 offset:55296
	ds_read_b128 v[216:219], v178 offset:18432
	ds_read_b128 v[220:223], v178 offset:23040
	ds_read_b128 v[224:227], v96 offset:59904
	ds_read_b128 v[228:231], v96 offset:55328
	ds_read_b128 v[244:247], v178 offset:18464
	ds_read_b128 v[252:255], v178 offset:23072
	s_waitcnt lgkmcnt(5)
	v_mfma_f32_32x32x16_bf16 v[32:47], v[212:215], v[216:219], v[32:47]
	s_waitcnt lgkmcnt(4)
	v_mfma_f32_32x32x16_bf16 v[48:63], v[212:215], v[220:223], v[48:63]
	ds_read_b128 v[212:215], v96 offset:59936
	s_waitcnt lgkmcnt(4)
	v_mfma_f32_32x32x16_bf16 v[16:31], v[224:227], v[216:219], v[16:31]
	ds_read_b128 v[216:219], v96 offset:55360
	v_mfma_f32_32x32x16_bf16 v[0:15], v[224:227], v[220:223], v[0:15]
	ds_read_b128 v[224:227], v178 offset:18496
	ds_read_b128 v[220:223], v178 offset:23104
	s_waitcnt lgkmcnt(5)
	v_mfma_f32_32x32x16_bf16 v[32:47], v[228:231], v[244:247], v[32:47]
	s_waitcnt lgkmcnt(4)
	v_mfma_f32_32x32x16_bf16 v[48:63], v[228:231], v[252:255], v[48:63]
	ds_read_b128 v[228:231], v96 offset:59968
	s_waitcnt lgkmcnt(4)
	v_mfma_f32_32x32x16_bf16 v[16:31], v[212:215], v[244:247], v[16:31]
	ds_read_b128 v[244:247], v96 offset:55392
	v_mfma_f32_32x32x16_bf16 v[0:15], v[212:215], v[252:255], v[0:15]
	ds_read_b128 v[212:215], v178 offset:18528
	ds_read_b128 v[252:255], v178 offset:23136
	s_waitcnt lgkmcnt(5)
	v_mfma_f32_32x32x16_bf16 v[32:47], v[216:219], v[224:227], v[32:47]
	s_waitcnt vmcnt(15)
	ds_write_b128 v177, v[64:67]
	global_load_dwordx4 v[64:67], v[152:153], off offset:1536
	s_waitcnt lgkmcnt(5)
	v_mfma_f32_32x32x16_bf16 v[48:63], v[216:219], v[220:223], v[48:63]
	ds_read_b128 v[216:219], v96 offset:60000
	s_waitcnt vmcnt(15)
	ds_write_b128 v177, v[72:75] offset:4608
	global_load_dwordx4 v[72:75], v[154:155], off offset:1536
	s_waitcnt lgkmcnt(6)
	v_mfma_f32_32x32x16_bf16 v[16:31], v[228:231], v[224:227], v[16:31]
	s_waitcnt vmcnt(15)
	ds_write_b128 v177, v[76:79] offset:9216
	global_load_dwordx4 v[76:79], v[156:157], off offset:1536
	v_mfma_f32_32x32x16_bf16 v[0:15], v[228:231], v[220:223], v[0:15]
	s_waitcnt vmcnt(15)
	ds_write_b128 v177, v[80:83] offset:13824
	global_load_dwordx4 v[80:83], v[158:159], off offset:1536
	s_waitcnt lgkmcnt(6)
	v_mfma_f32_32x32x16_bf16 v[32:47], v[244:247], v[212:215], v[32:47]
	s_waitcnt vmcnt(15)
	ds_write_b128 v177, v[102:105] offset:36864
	global_load_dwordx4 v[114:117], v[150:151], off offset:1536
	s_waitcnt lgkmcnt(6)
	v_mfma_f32_32x32x16_bf16 v[48:63], v[244:247], v[252:255], v[48:63]
	s_waitcnt vmcnt(15)
	ds_write_b128 v177, v[118:121] offset:41472
	s_waitcnt vmcnt(14)
	ds_write_b128 v177, v[122:125] offset:46080
	s_waitcnt lgkmcnt(6)
	v_mfma_f32_32x32x16_bf16 v[16:31], v[216:219], v[212:215], v[16:31]
	global_load_dwordx4 v[122:125], v[160:161], off offset:1536
	s_waitcnt vmcnt(14)
	ds_write_b128 v177, v[126:129] offset:50688
	v_mfma_f32_32x32x16_bf16 v[0:15], v[216:219], v[252:255], v[0:15]
	global_load_dwordx4 v[126:129], v[170:171], off offset:1536
	global_load_dwordx4 v[134:137], v[172:173], off offset:1536
	s_setprio 0
	s_waitcnt lgkmcnt(0)
	s_barrier
	s_setprio 1
	ds_read_b128 v[212:215], v96 offset:36864
	ds_read_b128 v[216:219], v178
	ds_read_b128 v[220:223], v178 offset:4608
	ds_read_b128 v[224:227], v96 offset:41472
	ds_read_b128 v[228:231], v96 offset:36896
	ds_read_b128 v[244:247], v178 offset:32
	ds_read_b128 v[252:255], v178 offset:4640
	s_waitcnt lgkmcnt(5)
	v_mfma_f32_32x32x16_bf16 v[32:47], v[212:215], v[216:219], v[32:47]
	s_waitcnt lgkmcnt(4)
	v_mfma_f32_32x32x16_bf16 v[48:63], v[212:215], v[220:223], v[48:63]
	ds_read_b128 v[212:215], v96 offset:41504
	s_waitcnt lgkmcnt(4)
	v_mfma_f32_32x32x16_bf16 v[16:31], v[224:227], v[216:219], v[16:31]
	ds_read_b128 v[216:219], v96 offset:36928
	v_mfma_f32_32x32x16_bf16 v[0:15], v[224:227], v[220:223], v[0:15]
	ds_read_b128 v[224:227], v178 offset:64
	ds_read_b128 v[220:223], v178 offset:4672
	s_waitcnt lgkmcnt(5)
	v_mfma_f32_32x32x16_bf16 v[32:47], v[228:231], v[244:247], v[32:47]
	s_waitcnt lgkmcnt(4)
	v_mfma_f32_32x32x16_bf16 v[48:63], v[228:231], v[252:255], v[48:63]
	ds_read_b128 v[228:231], v96 offset:41536
	s_waitcnt lgkmcnt(4)
	v_mfma_f32_32x32x16_bf16 v[16:31], v[212:215], v[244:247], v[16:31]
	ds_read_b128 v[244:247], v96 offset:36960
	v_mfma_f32_32x32x16_bf16 v[0:15], v[212:215], v[252:255], v[0:15]
	ds_read_b128 v[212:215], v178 offset:96
	ds_read_b128 v[252:255], v178 offset:4704
	s_waitcnt lgkmcnt(5)
	v_mfma_f32_32x32x16_bf16 v[32:47], v[216:219], v[224:227], v[32:47]
	s_waitcnt vmcnt(15)
	ds_write_b128 v177, v[68:71] offset:18432
	s_waitcnt vmcnt(14)
	ds_write_b128 v177, v[84:87] offset:23040
	s_waitcnt lgkmcnt(6)
	v_mfma_f32_32x32x16_bf16 v[48:63], v[216:219], v[220:223], v[48:63]
	ds_read_b128 v[216:219], v96 offset:41568
	s_waitcnt vmcnt(13)
	ds_write_b128 v177, v[88:91] offset:27648
	s_waitcnt vmcnt(12)
	ds_write_b128 v177, v[92:95] offset:32256
	s_waitcnt lgkmcnt(8)
	v_mfma_f32_32x32x16_bf16 v[16:31], v[228:231], v[224:227], v[16:31]
	s_waitcnt vmcnt(11)
	ds_write_b128 v177, v[98:101] offset:55296
	v_mfma_f32_32x32x16_bf16 v[0:15], v[228:231], v[220:223], v[0:15]
	global_load_dwordx4 v[98:101], v[152:153], off offset:1664
	global_load_dwordx4 v[102:105], v[154:155], off offset:1664
	s_waitcnt vmcnt(12)
	ds_write_b128 v177, v[106:109] offset:59904
	s_waitcnt lgkmcnt(8)
	v_mfma_f32_32x32x16_bf16 v[32:47], v[244:247], v[212:215], v[32:47]
	global_load_dwordx4 v[106:109], v[156:157], off offset:1664
	s_waitcnt vmcnt(12)
	ds_write_b128 v177, v[110:113] offset:64512
	s_waitcnt lgkmcnt(8)
	v_mfma_f32_32x32x16_bf16 v[48:63], v[244:247], v[252:255], v[48:63]
	global_load_dwordx4 v[110:113], v[158:159], off offset:1664
	global_load_dwordx4 v[118:121], v[150:151], off offset:1664
	s_waitcnt lgkmcnt(5)
	v_mfma_f32_32x32x16_bf16 v[16:31], v[216:219], v[212:215], v[16:31]
	s_waitcnt vmcnt(13)
	ds_write_b128 v179, v[130:133] offset:13824
	global_load_dwordx4 v[130:133], v[160:161], off offset:1664
	v_mfma_f32_32x32x16_bf16 v[0:15], v[216:219], v[252:255], v[0:15]
	global_load_dwordx4 v[138:141], v[170:171], off offset:1664
	global_load_dwordx4 v[142:145], v[172:173], off offset:1664
	s_setprio 0
	s_waitcnt lgkmcnt(0)
	s_barrier
	s_setprio 1
	ds_read_b128 v[212:215], v96 offset:55296
	ds_read_b128 v[216:219], v178 offset:18432
	ds_read_b128 v[220:223], v178 offset:23040
	ds_read_b128 v[224:227], v96 offset:59904
	ds_read_b128 v[228:231], v96 offset:55328
	ds_read_b128 v[244:247], v178 offset:18464
	ds_read_b128 v[252:255], v178 offset:23072
	s_waitcnt lgkmcnt(5)
	v_mfma_f32_32x32x16_bf16 v[32:47], v[212:215], v[216:219], v[32:47]
	s_waitcnt lgkmcnt(4)
	v_mfma_f32_32x32x16_bf16 v[48:63], v[212:215], v[220:223], v[48:63]
	ds_read_b128 v[212:215], v96 offset:59936
	s_waitcnt lgkmcnt(4)
	v_mfma_f32_32x32x16_bf16 v[16:31], v[224:227], v[216:219], v[16:31]
	ds_read_b128 v[216:219], v96 offset:55360
	v_mfma_f32_32x32x16_bf16 v[0:15], v[224:227], v[220:223], v[0:15]
	ds_read_b128 v[224:227], v178 offset:18496
	ds_read_b128 v[220:223], v178 offset:23104
	s_waitcnt lgkmcnt(5)
	v_mfma_f32_32x32x16_bf16 v[32:47], v[228:231], v[244:247], v[32:47]
	s_waitcnt lgkmcnt(4)
	v_mfma_f32_32x32x16_bf16 v[48:63], v[228:231], v[252:255], v[48:63]
	ds_read_b128 v[228:231], v96 offset:59968
	s_waitcnt lgkmcnt(4)
	v_mfma_f32_32x32x16_bf16 v[16:31], v[212:215], v[244:247], v[16:31]
	ds_read_b128 v[244:247], v96 offset:55392
	v_mfma_f32_32x32x16_bf16 v[0:15], v[212:215], v[252:255], v[0:15]
	ds_read_b128 v[212:215], v178 offset:18528
	ds_read_b128 v[252:255], v178 offset:23136
	s_waitcnt lgkmcnt(5)
	v_mfma_f32_32x32x16_bf16 v[32:47], v[216:219], v[224:227], v[32:47]
	s_waitcnt vmcnt(15)
	ds_write_b128 v177, v[64:67]
	global_load_dwordx4 v[64:67], v[152:153], off offset:1792
	s_waitcnt lgkmcnt(5)
	v_mfma_f32_32x32x16_bf16 v[48:63], v[216:219], v[220:223], v[48:63]
	ds_read_b128 v[216:219], v96 offset:60000
	s_waitcnt vmcnt(15)
	ds_write_b128 v177, v[72:75] offset:4608
	global_load_dwordx4 v[68:71], v[154:155], off offset:1792
	s_waitcnt lgkmcnt(6)
	v_mfma_f32_32x32x16_bf16 v[16:31], v[228:231], v[224:227], v[16:31]
	s_waitcnt vmcnt(15)
	ds_write_b128 v177, v[76:79] offset:9216
	global_load_dwordx4 v[72:75], v[156:157], off offset:1792
	v_mfma_f32_32x32x16_bf16 v[0:15], v[228:231], v[220:223], v[0:15]
	s_waitcnt vmcnt(15)
	ds_write_b128 v177, v[80:83] offset:13824
	global_load_dwordx4 v[76:79], v[158:159], off offset:1792
	s_waitcnt lgkmcnt(6)
	v_mfma_f32_32x32x16_bf16 v[32:47], v[244:247], v[212:215], v[32:47]
	s_waitcnt vmcnt(15)
	ds_write_b128 v177, v[114:117] offset:36864
	global_load_dwordx4 v[80:83], v[150:151], off offset:1792
	s_waitcnt lgkmcnt(6)
	v_mfma_f32_32x32x16_bf16 v[48:63], v[244:247], v[252:255], v[48:63]
	s_waitcnt vmcnt(15)
	ds_write_b128 v177, v[122:125] offset:41472
	global_load_dwordx4 v[84:87], v[160:161], off offset:1792
	s_waitcnt lgkmcnt(5)
	v_mfma_f32_32x32x16_bf16 v[16:31], v[216:219], v[212:215], v[16:31]
	s_waitcnt vmcnt(15)
	ds_write_b128 v177, v[126:129] offset:46080
	global_load_dwordx4 v[88:91], v[170:171], off offset:1792
	v_mfma_f32_32x32x16_bf16 v[0:15], v[216:219], v[252:255], v[0:15]
	s_waitcnt vmcnt(15)
	ds_write_b128 v177, v[134:137] offset:50688
	global_load_dwordx4 v[92:95], v[172:173], off offset:1792
	s_setprio 0
	s_waitcnt lgkmcnt(0)
	s_barrier
	s_setprio 1
	ds_read_b128 v[212:215], v96 offset:36864
	ds_read_b128 v[216:219], v178
	ds_read_b128 v[220:223], v178 offset:4608
	ds_read_b128 v[224:227], v96 offset:41472
	ds_read_b128 v[228:231], v96 offset:36896
	ds_read_b128 v[244:247], v178 offset:32
	ds_read_b128 v[252:255], v178 offset:4640
	s_waitcnt lgkmcnt(5)
	v_mfma_f32_32x32x16_bf16 v[32:47], v[212:215], v[216:219], v[32:47]
	s_waitcnt lgkmcnt(4)
	v_mfma_f32_32x32x16_bf16 v[48:63], v[212:215], v[220:223], v[48:63]
	ds_read_b128 v[212:215], v96 offset:41504
	s_waitcnt lgkmcnt(4)
	v_mfma_f32_32x32x16_bf16 v[16:31], v[224:227], v[216:219], v[16:31]
	ds_read_b128 v[216:219], v96 offset:36928
	v_mfma_f32_32x32x16_bf16 v[0:15], v[224:227], v[220:223], v[0:15]
	ds_read_b128 v[224:227], v178 offset:64
	ds_read_b128 v[220:223], v178 offset:4672
	s_waitcnt lgkmcnt(5)
	v_mfma_f32_32x32x16_bf16 v[32:47], v[228:231], v[244:247], v[32:47]
	s_waitcnt lgkmcnt(4)
	v_mfma_f32_32x32x16_bf16 v[48:63], v[228:231], v[252:255], v[48:63]
	ds_read_b128 v[228:231], v96 offset:41536
	s_waitcnt lgkmcnt(4)
	v_mfma_f32_32x32x16_bf16 v[16:31], v[212:215], v[244:247], v[16:31]
	ds_read_b128 v[244:247], v96 offset:36960
	v_mfma_f32_32x32x16_bf16 v[0:15], v[212:215], v[252:255], v[0:15]
	ds_read_b128 v[212:215], v178 offset:96
	ds_read_b128 v[252:255], v178 offset:4704
	s_waitcnt lgkmcnt(5)
	v_mfma_f32_32x32x16_bf16 v[32:47], v[216:219], v[224:227], v[32:47]
	s_waitcnt vmcnt(15)
	ds_write_b128 v177, v[98:101] offset:18432
	s_waitcnt vmcnt(14)
	ds_write_b128 v177, v[102:105] offset:23040
	s_waitcnt lgkmcnt(6)
	v_mfma_f32_32x32x16_bf16 v[48:63], v[216:219], v[220:223], v[48:63]
	ds_read_b128 v[216:219], v96 offset:41568
	global_load_dwordx4 v[100:103], v[152:153], off offset:1920
	s_waitcnt vmcnt(14)
	ds_write_b128 v177, v[106:109] offset:27648
	s_waitcnt lgkmcnt(7)
	v_mfma_f32_32x32x16_bf16 v[16:31], v[228:231], v[224:227], v[16:31]
	global_load_dwordx4 v[104:107], v[154:155], off offset:1920
	s_waitcnt vmcnt(14)
	ds_write_b128 v177, v[110:113] offset:32256
	v_mfma_f32_32x32x16_bf16 v[0:15], v[228:231], v[220:223], v[0:15]
	global_load_dwordx4 v[108:111], v[156:157], off offset:1920
	s_waitcnt vmcnt(14)
	ds_write_b128 v177, v[118:121] offset:55296
	s_waitcnt lgkmcnt(7)
	v_mfma_f32_32x32x16_bf16 v[32:47], v[244:247], v[212:215], v[32:47]
	global_load_dwordx4 v[116:119], v[158:159], off offset:1920
	global_load_dwordx4 v[112:115], v[150:151], off offset:1920
	s_waitcnt lgkmcnt(6)
	v_mfma_f32_32x32x16_bf16 v[48:63], v[244:247], v[252:255], v[48:63]
	s_waitcnt vmcnt(15)
	ds_write_b128 v177, v[130:133] offset:59904
	global_load_dwordx4 v[120:123], v[160:161], off offset:1920
	s_waitcnt lgkmcnt(4)
	v_mfma_f32_32x32x16_bf16 v[16:31], v[216:219], v[212:215], v[16:31]
	s_waitcnt vmcnt(15)
	ds_write_b128 v177, v[138:141] offset:64512
	global_load_dwordx4 v[124:127], v[170:171], off offset:1920
	v_mfma_f32_32x32x16_bf16 v[0:15], v[216:219], v[252:255], v[0:15]
	s_waitcnt vmcnt(15)
	ds_write_b128 v179, v[142:145] offset:13824
	global_load_dwordx4 v[128:131], v[172:173], off offset:1920
	s_setprio 0
	s_waitcnt lgkmcnt(0)
	s_barrier
	s_setprio 1
	ds_read_b128 v[212:215], v96 offset:55296
	ds_read_b128 v[216:219], v178 offset:18432
	ds_read_b128 v[220:223], v178 offset:23040
	ds_read_b128 v[224:227], v96 offset:59904
	ds_read_b128 v[228:231], v96 offset:55328
	ds_read_b128 v[244:247], v178 offset:18464
	ds_read_b128 v[252:255], v178 offset:23072
	s_waitcnt lgkmcnt(5)
	v_mfma_f32_32x32x16_bf16 v[32:47], v[212:215], v[216:219], v[32:47]
	s_waitcnt lgkmcnt(4)
	v_mfma_f32_32x32x16_bf16 v[48:63], v[212:215], v[220:223], v[48:63]
	ds_read_b128 v[212:215], v96 offset:59936
	s_waitcnt lgkmcnt(4)
	v_mfma_f32_32x32x16_bf16 v[16:31], v[224:227], v[216:219], v[16:31]
	ds_read_b128 v[216:219], v96 offset:55360
	v_mfma_f32_32x32x16_bf16 v[0:15], v[224:227], v[220:223], v[0:15]
	ds_read_b128 v[224:227], v178 offset:18496
	ds_read_b128 v[220:223], v178 offset:23104
	s_waitcnt lgkmcnt(5)
	v_mfma_f32_32x32x16_bf16 v[32:47], v[228:231], v[244:247], v[32:47]
	s_waitcnt lgkmcnt(4)
	v_mfma_f32_32x32x16_bf16 v[48:63], v[228:231], v[252:255], v[48:63]
	ds_read_b128 v[228:231], v96 offset:59968
	s_waitcnt lgkmcnt(4)
	v_mfma_f32_32x32x16_bf16 v[16:31], v[212:215], v[244:247], v[16:31]
	ds_read_b128 v[244:247], v96 offset:55392
	v_mfma_f32_32x32x16_bf16 v[0:15], v[212:215], v[252:255], v[0:15]
	ds_read_b128 v[212:215], v178 offset:18528
	ds_read_b128 v[252:255], v178 offset:23136
	s_waitcnt lgkmcnt(5)
	v_mfma_f32_32x32x16_bf16 v[32:47], v[216:219], v[224:227], v[32:47]
	s_waitcnt lgkmcnt(4)
	v_mfma_f32_32x32x16_bf16 v[48:63], v[216:219], v[220:223], v[48:63]
	ds_read_b128 v[216:219], v96 offset:60000
	s_waitcnt lgkmcnt(4)
	v_mfma_f32_32x32x16_bf16 v[16:31], v[228:231], v[224:227], v[16:31]
	v_mfma_f32_32x32x16_bf16 v[0:15], v[228:231], v[220:223], v[0:15]
	s_waitcnt lgkmcnt(2)
	v_mfma_f32_32x32x16_bf16 v[32:47], v[244:247], v[212:215], v[32:47]
	s_waitcnt lgkmcnt(1)
	v_mfma_f32_32x32x16_bf16 v[48:63], v[244:247], v[252:255], v[48:63]
	s_waitcnt lgkmcnt(0)
	v_mfma_f32_32x32x16_bf16 v[16:31], v[216:219], v[212:215], v[16:31]
	v_mfma_f32_32x32x16_bf16 v[0:15], v[216:219], v[252:255], v[0:15]
	s_setprio 0
	v_cndmask_b32_e64 v98, 0, 1, s[12:13]
	v_cmp_ne_u32_e64 s[38:39], 1, v98
	s_andn2_b64 vcc, exec, s[12:13]
	s_waitcnt vmcnt(15)
	ds_write_b128 v177, v[64:67]
	s_waitcnt vmcnt(14)
	ds_write_b128 v177, v[68:71] offset:4608
	s_waitcnt vmcnt(13)
	ds_write_b128 v177, v[72:75] offset:9216
	s_waitcnt vmcnt(12)
	ds_write_b128 v177, v[76:79] offset:13824
	s_waitcnt vmcnt(11)
	ds_write_b128 v177, v[80:83] offset:36864
	s_waitcnt vmcnt(10)
	ds_write_b128 v177, v[84:87] offset:41472
	s_waitcnt vmcnt(9)
	ds_write_b128 v177, v[88:91] offset:46080
	s_waitcnt vmcnt(8)
	ds_write_b128 v177, v[92:95] offset:50688
	s_cbranch_vccnz .LBB0_1239
	v_add_co_u32_e32 v68, vcc, 0x10000, v148
	global_load_dwordx4 v[64:67], v[148:149], off
	s_nop 0
	v_addc_co_u32_e32 v69, vcc, 0, v149, vcc
	v_add_co_u32_e32 v72, vcc, 0x20000, v148
	s_nop 1
	v_addc_co_u32_e32 v73, vcc, 0, v149, vcc
	v_add_co_u32_e32 v76, vcc, 0x30000, v148
	global_load_dwordx4 v[68:71], v[68:69], off
	global_load_dwordx4 v[72:75], v[72:73], off
	v_addc_co_u32_e32 v77, vcc, 0, v149, vcc
	v_add_co_u32_e32 v84, vcc, 0x10000, v146
	global_load_dwordx4 v[76:79], v[76:77], off
	s_nop 0
	global_load_dwordx4 v[80:83], v[146:147], off
	v_addc_co_u32_e32 v85, vcc, 0, v147, vcc
	v_add_co_u32_e32 v88, vcc, 0x20000, v146
	s_nop 1
	v_addc_co_u32_e32 v89, vcc, 0, v147, vcc
	v_add_co_u32_e32 v92, vcc, 0x30000, v146
	global_load_dwordx4 v[84:87], v[84:85], off
	s_nop 0
	global_load_dwordx4 v[88:91], v[88:89], off
	v_addc_co_u32_e32 v93, vcc, 0, v147, vcc
	global_load_dwordx4 v[92:95], v[92:93], off
.LBB0_1239:
	s_waitcnt lgkmcnt(0)
	s_barrier
	s_setprio 1
	ds_read_b128 v[212:215], v96 offset:36864
	ds_read_b128 v[216:219], v178
	ds_read_b128 v[220:223], v178 offset:4608
	ds_read_b128 v[224:227], v96 offset:41472
	ds_read_b128 v[228:231], v96 offset:36896
	ds_read_b128 v[244:247], v178 offset:32
	ds_read_b128 v[252:255], v178 offset:4640
	s_waitcnt lgkmcnt(5)
	v_mfma_f32_32x32x16_bf16 v[32:47], v[212:215], v[216:219], v[32:47]
	s_waitcnt lgkmcnt(4)
	v_mfma_f32_32x32x16_bf16 v[48:63], v[212:215], v[220:223], v[48:63]
	ds_read_b128 v[212:215], v96 offset:41504
	s_waitcnt lgkmcnt(4)
	v_mfma_f32_32x32x16_bf16 v[16:31], v[224:227], v[216:219], v[16:31]
	ds_read_b128 v[216:219], v96 offset:36928
	v_mfma_f32_32x32x16_bf16 v[0:15], v[224:227], v[220:223], v[0:15]
	ds_read_b128 v[224:227], v178 offset:64
	ds_read_b128 v[220:223], v178 offset:4672
	s_waitcnt lgkmcnt(5)
	v_mfma_f32_32x32x16_bf16 v[32:47], v[228:231], v[244:247], v[32:47]
	s_waitcnt lgkmcnt(4)
	v_mfma_f32_32x32x16_bf16 v[48:63], v[228:231], v[252:255], v[48:63]
	ds_read_b128 v[228:231], v96 offset:41536
	s_waitcnt lgkmcnt(4)
	v_mfma_f32_32x32x16_bf16 v[16:31], v[212:215], v[244:247], v[16:31]
	ds_read_b128 v[244:247], v96 offset:36960
	v_mfma_f32_32x32x16_bf16 v[0:15], v[212:215], v[252:255], v[0:15]
	ds_read_b128 v[212:215], v178 offset:96
	ds_read_b128 v[252:255], v178 offset:4704
	s_waitcnt lgkmcnt(5)
	v_mfma_f32_32x32x16_bf16 v[32:47], v[216:219], v[224:227], v[32:47]
	s_waitcnt lgkmcnt(4)
	v_mfma_f32_32x32x16_bf16 v[48:63], v[216:219], v[220:223], v[48:63]
	ds_read_b128 v[216:219], v96 offset:41568
	s_waitcnt lgkmcnt(4)
	v_mfma_f32_32x32x16_bf16 v[16:31], v[228:231], v[224:227], v[16:31]
	v_mfma_f32_32x32x16_bf16 v[0:15], v[228:231], v[220:223], v[0:15]
	s_waitcnt lgkmcnt(2)
	v_mfma_f32_32x32x16_bf16 v[32:47], v[244:247], v[212:215], v[32:47]
	s_waitcnt lgkmcnt(1)
	v_mfma_f32_32x32x16_bf16 v[48:63], v[244:247], v[252:255], v[48:63]
	s_waitcnt lgkmcnt(0)
	v_mfma_f32_32x32x16_bf16 v[16:31], v[216:219], v[212:215], v[16:31]
	v_mfma_f32_32x32x16_bf16 v[0:15], v[216:219], v[252:255], v[0:15]
	s_setprio 0
	s_and_b64 vcc, exec, s[38:39]
	s_waitcnt vmcnt(7)
	ds_write_b128 v177, v[100:103] offset:18432
	s_waitcnt vmcnt(6)
	ds_write_b128 v177, v[104:107] offset:23040
	s_waitcnt vmcnt(5)
	ds_write_b128 v177, v[108:111] offset:27648
	s_waitcnt vmcnt(4)
	ds_write_b128 v177, v[116:119] offset:32256
	s_waitcnt vmcnt(3)
	ds_write_b128 v177, v[112:115] offset:55296
	s_waitcnt vmcnt(2)
	ds_write_b128 v177, v[120:123] offset:59904
	s_waitcnt vmcnt(1)
	ds_write_b128 v177, v[124:127] offset:64512
	s_waitcnt vmcnt(0)
	ds_write_b128 v179, v[128:131] offset:13824
	s_cbranch_vccnz .LBB0_1241
	v_add_co_u32_e32 v98, vcc, 0x10000, v148
	global_load_dwordx4 v[100:103], v[148:149], off offset:128
	s_nop 0
	v_addc_co_u32_e32 v99, vcc, 0, v149, vcc
	v_add_co_u32_e32 v108, vcc, 0x20000, v148
	s_nop 1
	v_addc_co_u32_e32 v109, vcc, 0, v149, vcc
	global_load_dwordx4 v[104:107], v[98:99], off offset:128
	global_load_dwordx4 v[108:111], v[108:109], off offset:128
	v_add_co_u32_e32 v98, vcc, 0x30000, v148
	s_nop 1
	v_addc_co_u32_e32 v99, vcc, 0, v149, vcc
	global_load_dwordx4 v[116:119], v[98:99], off offset:128
	global_load_dwordx4 v[112:115], v[146:147], off offset:128
	v_add_co_u32_e32 v98, vcc, 0x10000, v146
	s_nop 1
	v_addc_co_u32_e32 v99, vcc, 0, v147, vcc
	v_add_co_u32_e32 v124, vcc, 0x20000, v146
	s_nop 1
	v_addc_co_u32_e32 v125, vcc, 0, v147, vcc
	global_load_dwordx4 v[120:123], v[98:99], off offset:128
	s_nop 0
	global_load_dwordx4 v[124:127], v[124:125], off offset:128
	v_add_co_u32_e32 v98, vcc, 0x30000, v146
	s_nop 1
	v_addc_co_u32_e32 v99, vcc, 0, v147, vcc
	global_load_dwordx4 v[128:131], v[98:99], off offset:128
.LBB0_1241:
	s_waitcnt lgkmcnt(0)
	s_barrier
	s_setprio 1
	ds_read_b128 v[212:215], v96 offset:55296
	ds_read_b128 v[216:219], v178 offset:18432
	ds_read_b128 v[220:223], v178 offset:23040
	ds_read_b128 v[224:227], v96 offset:59904
	ds_read_b128 v[228:231], v96 offset:55328
	ds_read_b128 v[244:247], v178 offset:18464
	ds_read_b128 v[252:255], v178 offset:23072
	s_waitcnt lgkmcnt(5)
	v_mfma_f32_32x32x16_bf16 v[32:47], v[212:215], v[216:219], v[32:47]
	s_waitcnt lgkmcnt(4)
	v_mfma_f32_32x32x16_bf16 v[48:63], v[212:215], v[220:223], v[48:63]
	ds_read_b128 v[212:215], v96 offset:59936
	s_waitcnt lgkmcnt(4)
	v_mfma_f32_32x32x16_bf16 v[16:31], v[224:227], v[216:219], v[16:31]
	ds_read_b128 v[216:219], v96 offset:55360
	v_mfma_f32_32x32x16_bf16 v[0:15], v[224:227], v[220:223], v[0:15]
	ds_read_b128 v[224:227], v178 offset:18496
	ds_read_b128 v[220:223], v178 offset:23104
	s_waitcnt lgkmcnt(5)
	v_mfma_f32_32x32x16_bf16 v[32:47], v[228:231], v[244:247], v[32:47]
	s_waitcnt lgkmcnt(4)
	v_mfma_f32_32x32x16_bf16 v[48:63], v[228:231], v[252:255], v[48:63]
	ds_read_b128 v[228:231], v96 offset:59968
	s_waitcnt lgkmcnt(4)
	v_mfma_f32_32x32x16_bf16 v[16:31], v[212:215], v[244:247], v[16:31]
	ds_read_b128 v[244:247], v96 offset:55392
	v_mfma_f32_32x32x16_bf16 v[0:15], v[212:215], v[252:255], v[0:15]
	ds_read_b128 v[212:215], v178 offset:18528
	ds_read_b128 v[252:255], v178 offset:23136
	s_waitcnt lgkmcnt(5)
	v_mfma_f32_32x32x16_bf16 v[32:47], v[216:219], v[224:227], v[32:47]
	s_waitcnt lgkmcnt(4)
	v_mfma_f32_32x32x16_bf16 v[48:63], v[216:219], v[220:223], v[48:63]
	ds_read_b128 v[216:219], v96 offset:60000
	s_waitcnt lgkmcnt(4)
	v_mfma_f32_32x32x16_bf16 v[16:31], v[228:231], v[224:227], v[16:31]
	v_mfma_f32_32x32x16_bf16 v[0:15], v[228:231], v[220:223], v[0:15]
	s_waitcnt lgkmcnt(2)
	v_mfma_f32_32x32x16_bf16 v[32:47], v[244:247], v[212:215], v[32:47]
	s_waitcnt lgkmcnt(1)
	v_mfma_f32_32x32x16_bf16 v[48:63], v[244:247], v[252:255], v[48:63]
	s_waitcnt lgkmcnt(0)
	v_mfma_f32_32x32x16_bf16 v[16:31], v[216:219], v[212:215], v[16:31]
	v_mfma_f32_32x32x16_bf16 v[0:15], v[216:219], v[252:255], v[0:15]
	s_setprio 0
	s_and_b64 vcc, exec, s[38:39]
	s_cbranch_vccnz .LBB0_1232
	ds_write_b128 v177, v[64:67]
	ds_write_b128 v177, v[68:71] offset:4608
	ds_write_b128 v177, v[72:75] offset:9216
	ds_write_b128 v177, v[76:79] offset:13824
	ds_write_b128 v177, v[80:83] offset:36864
	ds_write_b128 v177, v[84:87] offset:41472
	ds_write_b128 v177, v[88:91] offset:46080
	ds_write_b128 v177, v[92:95] offset:50688
	v_add_co_u32_e32 v68, vcc, 0x10000, v148
	global_load_dwordx4 v[64:67], v[148:149], off offset:256
	s_nop 0
	v_addc_co_u32_e32 v69, vcc, 0, v149, vcc
	v_add_co_u32_e32 v72, vcc, 0x20000, v148
	s_nop 1
	v_addc_co_u32_e32 v73, vcc, 0, v149, vcc
	v_add_co_u32_e32 v76, vcc, 0x30000, v148
	global_load_dwordx4 v[68:71], v[68:69], off offset:256
	s_nop 0
	global_load_dwordx4 v[72:75], v[72:73], off offset:256
	v_addc_co_u32_e32 v77, vcc, 0, v149, vcc
	v_add_co_u32_e32 v84, vcc, 0x10000, v146
	global_load_dwordx4 v[76:79], v[76:77], off offset:256
	global_load_dwordx4 v[80:83], v[146:147], off offset:256
	v_addc_co_u32_e32 v85, vcc, 0, v147, vcc
	v_add_co_u32_e32 v88, vcc, 0x20000, v146
	s_nop 1
	v_addc_co_u32_e32 v89, vcc, 0, v147, vcc
	v_add_co_u32_e32 v92, vcc, 0x30000, v146
	global_load_dwordx4 v[84:87], v[84:85], off offset:256
	global_load_dwordx4 v[88:91], v[88:89], off offset:256
	v_addc_co_u32_e32 v93, vcc, 0, v147, vcc
	global_load_dwordx4 v[92:95], v[92:93], off offset:256
	s_branch .LBB0_1232

.LBB0_1245:
	s_ashr_i32 s2, s12, 1
	s_add_i32 s2, s2, s4
	s_ashr_i32 s3, s2, 31
	s_lshr_b32 s3, s3, 24
	s_add_i32 s3, s2, s3
	s_ashr_i32 s6, s3, 8
	s_lshl_b32 s6, s6, 5
	s_sub_i32 s7, s10, s6
	s_min_i32 s7, s7, 32
	s_abs_i32 s38, s7
	v_cvt_f32_u32_e32 v0, s38
	s_sub_i32 s39, 0, s38
	s_and_b32 s3, s3, 0xffffff00
	s_sub_i32 s2, s2, s3
	v_rcp_iflag_f32_e32 v0, v0
	s_abs_i32 s13, s2
	s_xor_b32 s3, s2, s7
	s_ashr_i32 s3, s3, 31
	v_mul_f32_e32 v0, 0x4f7ffffe, v0
	v_cvt_u32_f32_e32 v0, v0
	v_mov_b32_e32 v3, v162
	v_readfirstlane_b32 s40, v0
	s_mul_i32 s39, s39, s40
	s_mul_hi_u32 s39, s40, s39
	s_add_i32 s40, s40, s39
	s_mul_hi_u32 s39, s13, s40
	s_mul_i32 s40, s39, s38
	s_sub_i32 s13, s13, s40
	s_add_i32 s40, s39, 1
	s_sub_i32 s41, s13, s38
	s_cmp_ge_u32 s13, s38
	s_cselect_b32 s39, s40, s39
	s_cselect_b32 s13, s41, s13
	s_add_i32 s40, s39, 1
	s_cmp_ge_u32 s13, s38
	s_cselect_b32 s13, s40, s39
	s_xor_b32 s13, s13, s3
	s_sub_i32 s3, s13, s3
	s_mul_i32 s7, s3, s7
	s_sub_i32 s2, s2, s7
	s_add_i32 s2, s6, s2
	s_lshl_b32 s3, s3, 1
	s_and_b32 s6, s12, 1
	s_or_b32 s6, s3, s6
	s_ashr_i32 s3, s2, 31
	s_lshl_b64 s[38:39], s[2:3], 18
	v_ashrrev_i32_e32 v0, 3, v3
	v_lshlrev_b32_e32 v1, 3, v3
	s_add_u32 s38, s44, s38
	v_and_b32_e32 v2, 56, v1
	v_ashrrev_i32_e32 v1, 31, v0
	s_addc_u32 s39, s45, s39
	v_lshlrev_b64 v[4:5], 11, v[0:1]
	v_lshl_add_u64 v[6:7], s[38:39], 0, v[4:5]
	v_lshlrev_b32_e32 v96, 1, v2
	s_ashr_i32 s7, s6, 31
	v_lshl_add_u64 v[90:91], v[6:7], 0, v[96:97]
	s_lshl_b64 s[40:41], s[6:7], 17
	v_add_co_u32_e32 v92, vcc, s8, v90
	s_add_u32 s40, s62, s40
	s_nop 0
	v_addc_co_u32_e32 v93, vcc, 0, v91, vcc
	s_addc_u32 s41, s63, s41
	v_add_co_u32_e32 v94, vcc, s9, v90
	v_lshl_add_u64 v[4:5], s[40:41], 0, v[4:5]
	v_mad_u64_u32 v[24:25], s[38:39], v0, s84, v[2:3]
	v_and_b32_e32 v1, 31, v3
	v_lshrrev_b32_e32 v2, 1, v3
	v_lshrrev_b32_e32 v0, 2, v3
	v_addc_co_u32_e32 v95, vcc, 0, v91, vcc
	v_lshl_add_u64 v[88:89], v[4:5], 0, v[96:97]
	v_and_or_b32 v4, v2, s81, v1
	v_and_b32_e32 v0, 8, v0
	v_add_co_u32_e32 v98, vcc, s16, v90
	v_mad_u64_u32 v[26:27], s[38:39], v4, s84, v[0:1]
	v_and_or_b32 v1, v2, 32, v1
	v_addc_co_u32_e32 v99, vcc, 0, v91, vcc
	v_mad_u32_u24 v25, v1, s84, v0
	global_load_dwordx4 v[0:3], v[90:91], off
	global_load_dwordx4 v[4:7], v[92:93], off
	global_load_dwordx4 v[8:11], v[94:95], off
	global_load_dwordx4 v[12:15], v[98:99], off
	global_load_dwordx4 v[16:19], v[88:89], off
	v_add_co_u32_e32 v100, vcc, s8, v88
	v_lshl_add_u32 v96, v24, 1, 0
	s_nop 0
	v_addc_co_u32_e32 v101, vcc, 0, v89, vcc
	global_load_dwordx4 v[20:23], v[100:101], off
	v_lshl_add_u32 v103, v26, 1, 0
	v_lshl_add_u32 v104, v25, 1, 0
	s_waitcnt vmcnt(5)
	ds_write_b128 v96, v[0:3]
	s_waitcnt vmcnt(4)
	ds_write_b128 v96, v[4:7] offset:4608
	s_waitcnt vmcnt(3)
	ds_write_b128 v96, v[8:11] offset:9216
	s_waitcnt vmcnt(2)
	ds_write_b128 v96, v[12:15] offset:13824
	s_waitcnt vmcnt(1)
	ds_write_b128 v96, v[16:19] offset:36864
	s_waitcnt vmcnt(0)
	ds_write_b128 v96, v[20:23] offset:41472
	global_load_dwordx4 v[56:59], v[90:91], off offset:128
	global_load_dwordx4 v[60:63], v[92:93], off offset:128
	global_load_dwordx4 v[64:67], v[94:95], off offset:128
	global_load_dwordx4 v[68:71], v[98:99], off offset:128
	global_load_dwordx4 v[72:75], v[88:89], off offset:128
	global_load_dwordx4 v[76:79], v[100:101], off offset:128
	global_load_dwordx4 v[32:35], v[90:91], off offset:256
	global_load_dwordx4 v[36:39], v[92:93], off offset:256
	global_load_dwordx4 v[40:43], v[94:95], off offset:256
	global_load_dwordx4 v[44:47], v[98:99], off offset:256
	global_load_dwordx4 v[48:51], v[88:89], off offset:256
	global_load_dwordx4 v[52:55], v[100:101], off offset:256
	s_waitcnt lgkmcnt(0)
	s_barrier
	s_setprio 1
	ds_read_b128 v[212:215], v104 offset:36864
	ds_read_b128 v[216:219], v103
	ds_read_b128 v[220:223], v103 offset:4608
	ds_read_b128 v[224:227], v104 offset:36896
	ds_read_b128 v[228:231], v103 offset:32
	ds_read_b128 v[244:247], v103 offset:4640
	ds_read_b128 v[252:255], v104 offset:36928
	s_waitcnt lgkmcnt(5)
	v_mfma_f32_32x32x16_bf16 v[0:15], v[212:215], v[216:219], 0
	ds_read_b128 v[216:219], v103 offset:64
	s_waitcnt lgkmcnt(5)
	v_mfma_f32_32x32x16_bf16 v[16:31], v[212:215], v[220:223], 0
	ds_read_b128 v[212:215], v103 offset:4672
	ds_read_b128 v[220:223], v104 offset:36960
	s_waitcnt lgkmcnt(5)
	v_mfma_f32_32x32x16_bf16 v[0:15], v[224:227], v[228:231], v[0:15]
	ds_read_b128 v[228:231], v103 offset:96
	s_waitcnt lgkmcnt(5)
	v_mfma_f32_32x32x16_bf16 v[16:31], v[224:227], v[244:247], v[16:31]
	ds_read_b128 v[224:227], v103 offset:4704
	s_waitcnt lgkmcnt(4)
	v_mfma_f32_32x32x16_bf16 v[0:15], v[252:255], v[216:219], v[0:15]
	s_waitcnt lgkmcnt(3)
	v_mfma_f32_32x32x16_bf16 v[16:31], v[252:255], v[212:215], v[16:31]
	s_waitcnt lgkmcnt(1)
	v_mfma_f32_32x32x16_bf16 v[0:15], v[220:223], v[228:231], v[0:15]
	s_waitcnt lgkmcnt(0)
	v_mfma_f32_32x32x16_bf16 v[16:31], v[220:223], v[224:227], v[16:31]
	s_waitcnt vmcnt(11)
	ds_write_b128 v96, v[56:59] offset:18432
	global_load_dwordx4 v[56:59], v[90:91], off offset:384
	s_waitcnt vmcnt(11)
	ds_write_b128 v96, v[60:63] offset:23040
	global_load_dwordx4 v[60:63], v[92:93], off offset:384
	s_waitcnt vmcnt(11)
	ds_write_b128 v96, v[64:67] offset:27648
	global_load_dwordx4 v[64:67], v[94:95], off offset:384
	s_waitcnt vmcnt(11)
	ds_write_b128 v96, v[68:71] offset:32256
	global_load_dwordx4 v[68:71], v[98:99], off offset:384
	s_waitcnt vmcnt(11)
	ds_write_b128 v96, v[72:75] offset:55296
	global_load_dwordx4 v[72:75], v[88:89], off offset:384
	s_waitcnt vmcnt(11)
	ds_write_b128 v96, v[76:79] offset:59904
	global_load_dwordx4 v[80:83], v[100:101], off offset:384
	s_setprio 0
	s_waitcnt lgkmcnt(0)
	s_barrier
	s_setprio 1
	ds_read_b128 v[212:215], v104 offset:55296
	ds_read_b128 v[216:219], v103 offset:18432
	ds_read_b128 v[220:223], v103 offset:23040
	ds_read_b128 v[224:227], v104 offset:55328
	ds_read_b128 v[228:231], v103 offset:18464
	ds_read_b128 v[244:247], v103 offset:23072
	ds_read_b128 v[252:255], v104 offset:55360
	s_waitcnt lgkmcnt(5)
	v_mfma_f32_32x32x16_bf16 v[0:15], v[212:215], v[216:219], v[0:15]
	ds_read_b128 v[216:219], v103 offset:18496
	s_waitcnt lgkmcnt(5)
	v_mfma_f32_32x32x16_bf16 v[16:31], v[212:215], v[220:223], v[16:31]
	ds_read_b128 v[212:215], v103 offset:23104
	ds_read_b128 v[220:223], v104 offset:55392
	s_waitcnt lgkmcnt(5)
	v_mfma_f32_32x32x16_bf16 v[0:15], v[224:227], v[228:231], v[0:15]
	ds_read_b128 v[228:231], v103 offset:18528
	s_waitcnt lgkmcnt(5)
	v_mfma_f32_32x32x16_bf16 v[16:31], v[224:227], v[244:247], v[16:31]
	ds_read_b128 v[224:227], v103 offset:23136
	s_waitcnt lgkmcnt(4)
	v_mfma_f32_32x32x16_bf16 v[0:15], v[252:255], v[216:219], v[0:15]
	s_waitcnt lgkmcnt(3)
	v_mfma_f32_32x32x16_bf16 v[16:31], v[252:255], v[212:215], v[16:31]
	s_waitcnt lgkmcnt(1)
	v_mfma_f32_32x32x16_bf16 v[0:15], v[220:223], v[228:231], v[0:15]
	s_waitcnt lgkmcnt(0)
	v_mfma_f32_32x32x16_bf16 v[16:31], v[220:223], v[224:227], v[16:31]
	s_waitcnt vmcnt(11)
	ds_write_b128 v96, v[32:35]
	global_load_dwordx4 v[32:35], v[90:91], off offset:512
	s_waitcnt vmcnt(11)
	ds_write_b128 v96, v[36:39] offset:4608
	s_waitcnt vmcnt(10)
	ds_write_b128 v96, v[40:43] offset:9216
	global_load_dwordx4 v[40:43], v[92:93], off offset:512
	s_waitcnt vmcnt(10)
	ds_write_b128 v96, v[44:47] offset:13824
	global_load_dwordx4 v[44:47], v[94:95], off offset:512
	s_waitcnt vmcnt(10)
	ds_write_b128 v96, v[48:51] offset:36864
	global_load_dwordx4 v[48:51], v[98:99], off offset:512
	global_load_dwordx4 v[76:79], v[88:89], off offset:512
	s_waitcnt vmcnt(11)
	ds_write_b128 v96, v[52:55] offset:41472
	global_load_dwordx4 v[84:87], v[100:101], off offset:512
	s_setprio 0
	s_waitcnt lgkmcnt(0)
	s_barrier
	s_setprio 1
	ds_read_b128 v[212:215], v104 offset:36864
	ds_read_b128 v[216:219], v103
	ds_read_b128 v[220:223], v103 offset:4608
	ds_read_b128 v[224:227], v104 offset:36896
	ds_read_b128 v[228:231], v103 offset:32
	ds_read_b128 v[244:247], v103 offset:4640
	ds_read_b128 v[252:255], v104 offset:36928
	s_waitcnt lgkmcnt(5)
	v_mfma_f32_32x32x16_bf16 v[0:15], v[212:215], v[216:219], v[0:15]
	ds_read_b128 v[216:219], v103 offset:64
	s_waitcnt lgkmcnt(5)
	v_mfma_f32_32x32x16_bf16 v[16:31], v[212:215], v[220:223], v[16:31]
	ds_read_b128 v[212:215], v103 offset:4672
	ds_read_b128 v[220:223], v104 offset:36960
	s_waitcnt lgkmcnt(5)
	v_mfma_f32_32x32x16_bf16 v[0:15], v[224:227], v[228:231], v[0:15]
	ds_read_b128 v[228:231], v103 offset:96
	s_waitcnt lgkmcnt(5)
	v_mfma_f32_32x32x16_bf16 v[16:31], v[224:227], v[244:247], v[16:31]
	ds_read_b128 v[224:227], v103 offset:4704
	s_waitcnt lgkmcnt(4)
	v_mfma_f32_32x32x16_bf16 v[0:15], v[252:255], v[216:219], v[0:15]
	s_waitcnt lgkmcnt(3)
	v_mfma_f32_32x32x16_bf16 v[16:31], v[252:255], v[212:215], v[16:31]
	s_waitcnt lgkmcnt(1)
	v_mfma_f32_32x32x16_bf16 v[0:15], v[220:223], v[228:231], v[0:15]
	s_waitcnt lgkmcnt(0)
	v_mfma_f32_32x32x16_bf16 v[16:31], v[220:223], v[224:227], v[16:31]
	s_waitcnt vmcnt(11)
	ds_write_b128 v96, v[56:59] offset:18432
	global_load_dwordx4 v[36:39], v[90:91], off offset:640
	s_waitcnt vmcnt(11)
	ds_write_b128 v96, v[60:63] offset:23040
	global_load_dwordx4 v[52:55], v[92:93], off offset:640
	s_waitcnt vmcnt(11)
	ds_write_b128 v96, v[64:67] offset:27648
	global_load_dwordx4 v[56:59], v[94:95], off offset:640
	s_waitcnt vmcnt(11)
	ds_write_b128 v96, v[68:71] offset:32256
	global_load_dwordx4 v[60:63], v[98:99], off offset:640
	s_waitcnt vmcnt(11)
	ds_write_b128 v96, v[72:75] offset:55296
	global_load_dwordx4 v[64:67], v[88:89], off offset:640
	s_waitcnt vmcnt(11)
	ds_write_b128 v96, v[80:83] offset:59904
	global_load_dwordx4 v[72:75], v[100:101], off offset:640
	s_setprio 0
	s_waitcnt lgkmcnt(0)
	s_barrier
	s_setprio 1
	ds_read_b128 v[212:215], v104 offset:55296
	ds_read_b128 v[216:219], v103 offset:18432
	ds_read_b128 v[220:223], v103 offset:23040
	ds_read_b128 v[224:227], v104 offset:55328
	ds_read_b128 v[228:231], v103 offset:18464
	ds_read_b128 v[244:247], v103 offset:23072
	ds_read_b128 v[252:255], v104 offset:55360
	s_waitcnt lgkmcnt(5)
	v_mfma_f32_32x32x16_bf16 v[0:15], v[212:215], v[216:219], v[0:15]
	ds_read_b128 v[216:219], v103 offset:18496
	s_waitcnt lgkmcnt(5)
	v_mfma_f32_32x32x16_bf16 v[16:31], v[212:215], v[220:223], v[16:31]
	ds_read_b128 v[212:215], v103 offset:23104
	ds_read_b128 v[220:223], v104 offset:55392
	s_waitcnt lgkmcnt(5)
	v_mfma_f32_32x32x16_bf16 v[0:15], v[224:227], v[228:231], v[0:15]
	ds_read_b128 v[228:231], v103 offset:18528
	s_waitcnt lgkmcnt(5)
	v_mfma_f32_32x32x16_bf16 v[16:31], v[224:227], v[244:247], v[16:31]
	ds_read_b128 v[224:227], v103 offset:23136
	s_waitcnt lgkmcnt(4)
	v_mfma_f32_32x32x16_bf16 v[0:15], v[252:255], v[216:219], v[0:15]
	s_waitcnt lgkmcnt(3)
	v_mfma_f32_32x32x16_bf16 v[16:31], v[252:255], v[212:215], v[16:31]
	s_waitcnt lgkmcnt(1)
	v_mfma_f32_32x32x16_bf16 v[0:15], v[220:223], v[228:231], v[0:15]
	s_waitcnt lgkmcnt(0)
	v_mfma_f32_32x32x16_bf16 v[16:31], v[220:223], v[224:227], v[16:31]
	s_waitcnt vmcnt(11)
	ds_write_b128 v96, v[32:35]
	global_load_dwordx4 v[32:35], v[90:91], off offset:768
	s_waitcnt vmcnt(11)
	ds_write_b128 v96, v[40:43] offset:4608
	global_load_dwordx4 v[40:43], v[92:93], off offset:768
	s_waitcnt vmcnt(11)
	ds_write_b128 v96, v[44:47] offset:9216
	global_load_dwordx4 v[44:47], v[94:95], off offset:768
	s_waitcnt vmcnt(11)
	ds_write_b128 v96, v[48:51] offset:13824
	global_load_dwordx4 v[48:51], v[98:99], off offset:768
	s_waitcnt vmcnt(11)
	ds_write_b128 v96, v[76:79] offset:36864
	global_load_dwordx4 v[68:71], v[88:89], off offset:768
	s_waitcnt vmcnt(11)
	ds_write_b128 v96, v[84:87] offset:41472
	global_load_dwordx4 v[76:79], v[100:101], off offset:768
	s_setprio 0
	s_waitcnt lgkmcnt(0)
	s_barrier
	s_setprio 1
	ds_read_b128 v[212:215], v104 offset:36864
	ds_read_b128 v[216:219], v103
	ds_read_b128 v[220:223], v103 offset:4608
	ds_read_b128 v[224:227], v104 offset:36896
	ds_read_b128 v[228:231], v103 offset:32
	ds_read_b128 v[244:247], v103 offset:4640
	ds_read_b128 v[252:255], v104 offset:36928
	s_waitcnt lgkmcnt(5)
	v_mfma_f32_32x32x16_bf16 v[0:15], v[212:215], v[216:219], v[0:15]
	ds_read_b128 v[216:219], v103 offset:64
	s_waitcnt lgkmcnt(5)
	v_mfma_f32_32x32x16_bf16 v[16:31], v[212:215], v[220:223], v[16:31]
	ds_read_b128 v[212:215], v103 offset:4672
	ds_read_b128 v[220:223], v104 offset:36960
	s_waitcnt lgkmcnt(5)
	v_mfma_f32_32x32x16_bf16 v[0:15], v[224:227], v[228:231], v[0:15]
	ds_read_b128 v[228:231], v103 offset:96
	s_waitcnt lgkmcnt(5)
	v_mfma_f32_32x32x16_bf16 v[16:31], v[224:227], v[244:247], v[16:31]
	ds_read_b128 v[224:227], v103 offset:4704
	s_waitcnt lgkmcnt(4)
	v_mfma_f32_32x32x16_bf16 v[0:15], v[252:255], v[216:219], v[0:15]
	s_waitcnt lgkmcnt(3)
	v_mfma_f32_32x32x16_bf16 v[16:31], v[252:255], v[212:215], v[16:31]
	s_waitcnt lgkmcnt(1)
	v_mfma_f32_32x32x16_bf16 v[0:15], v[220:223], v[228:231], v[0:15]
	s_waitcnt lgkmcnt(0)
	v_mfma_f32_32x32x16_bf16 v[16:31], v[220:223], v[224:227], v[16:31]
	s_waitcnt vmcnt(11)
	ds_write_b128 v96, v[36:39] offset:18432
	global_load_dwordx4 v[36:39], v[90:91], off offset:896
	s_waitcnt vmcnt(11)
	ds_write_b128 v96, v[52:55] offset:23040
	global_load_dwordx4 v[52:55], v[92:93], off offset:896
	s_waitcnt vmcnt(11)
	ds_write_b128 v96, v[56:59] offset:27648
	global_load_dwordx4 v[56:59], v[94:95], off offset:896
	s_waitcnt vmcnt(11)
	ds_write_b128 v96, v[60:63] offset:32256
	global_load_dwordx4 v[60:63], v[98:99], off offset:896
	s_waitcnt vmcnt(11)
	ds_write_b128 v96, v[64:67] offset:55296
	global_load_dwordx4 v[64:67], v[88:89], off offset:896
	s_waitcnt vmcnt(11)
	ds_write_b128 v96, v[72:75] offset:59904
	global_load_dwordx4 v[72:75], v[100:101], off offset:896
	s_setprio 0
	s_waitcnt lgkmcnt(0)
	s_barrier
	s_setprio 1
	ds_read_b128 v[212:215], v104 offset:55296
	ds_read_b128 v[216:219], v103 offset:18432
	ds_read_b128 v[220:223], v103 offset:23040
	ds_read_b128 v[224:227], v104 offset:55328
	ds_read_b128 v[228:231], v103 offset:18464
	ds_read_b128 v[244:247], v103 offset:23072
	ds_read_b128 v[252:255], v104 offset:55360
	s_waitcnt lgkmcnt(5)
	v_mfma_f32_32x32x16_bf16 v[0:15], v[212:215], v[216:219], v[0:15]
	ds_read_b128 v[216:219], v103 offset:18496
	s_waitcnt lgkmcnt(5)
	v_mfma_f32_32x32x16_bf16 v[16:31], v[212:215], v[220:223], v[16:31]
	ds_read_b128 v[212:215], v103 offset:23104
	ds_read_b128 v[220:223], v104 offset:55392
	s_waitcnt lgkmcnt(5)
	v_mfma_f32_32x32x16_bf16 v[0:15], v[224:227], v[228:231], v[0:15]
	ds_read_b128 v[228:231], v103 offset:18528
	s_waitcnt lgkmcnt(5)
	v_mfma_f32_32x32x16_bf16 v[16:31], v[224:227], v[244:247], v[16:31]
	ds_read_b128 v[224:227], v103 offset:23136
	s_waitcnt lgkmcnt(4)
	v_mfma_f32_32x32x16_bf16 v[0:15], v[252:255], v[216:219], v[0:15]
	s_waitcnt lgkmcnt(3)
	v_mfma_f32_32x32x16_bf16 v[16:31], v[252:255], v[212:215], v[16:31]
	s_waitcnt lgkmcnt(1)
	v_mfma_f32_32x32x16_bf16 v[0:15], v[220:223], v[228:231], v[0:15]
	s_waitcnt lgkmcnt(0)
	v_mfma_f32_32x32x16_bf16 v[16:31], v[220:223], v[224:227], v[16:31]
	s_waitcnt vmcnt(11)
	ds_write_b128 v96, v[32:35]
	global_load_dwordx4 v[32:35], v[90:91], off offset:1024
	s_waitcnt vmcnt(11)
	ds_write_b128 v96, v[40:43] offset:4608
	global_load_dwordx4 v[40:43], v[92:93], off offset:1024
	s_waitcnt vmcnt(11)
	ds_write_b128 v96, v[44:47] offset:9216
	global_load_dwordx4 v[44:47], v[94:95], off offset:1024
	s_waitcnt vmcnt(11)
	ds_write_b128 v96, v[48:51] offset:13824
	global_load_dwordx4 v[48:51], v[98:99], off offset:1024
	s_waitcnt vmcnt(11)
	ds_write_b128 v96, v[68:71] offset:36864
	global_load_dwordx4 v[68:71], v[88:89], off offset:1024
	s_waitcnt vmcnt(11)
	ds_write_b128 v96, v[76:79] offset:41472
	global_load_dwordx4 v[76:79], v[100:101], off offset:1024
	s_setprio 0
	s_waitcnt lgkmcnt(0)
	s_barrier
	s_setprio 1
	ds_read_b128 v[212:215], v104 offset:36864
	ds_read_b128 v[216:219], v103
	ds_read_b128 v[220:223], v103 offset:4608
	ds_read_b128 v[224:227], v104 offset:36896
	ds_read_b128 v[228:231], v103 offset:32
	ds_read_b128 v[244:247], v103 offset:4640
	ds_read_b128 v[252:255], v104 offset:36928
	s_waitcnt lgkmcnt(5)
	v_mfma_f32_32x32x16_bf16 v[0:15], v[212:215], v[216:219], v[0:15]
	ds_read_b128 v[216:219], v103 offset:64
	s_waitcnt lgkmcnt(5)
	v_mfma_f32_32x32x16_bf16 v[16:31], v[212:215], v[220:223], v[16:31]
	ds_read_b128 v[212:215], v103 offset:4672
	ds_read_b128 v[220:223], v104 offset:36960
	s_waitcnt lgkmcnt(5)
	v_mfma_f32_32x32x16_bf16 v[0:15], v[224:227], v[228:231], v[0:15]
	ds_read_b128 v[228:231], v103 offset:96
	s_waitcnt lgkmcnt(5)
	v_mfma_f32_32x32x16_bf16 v[16:31], v[224:227], v[244:247], v[16:31]
	ds_read_b128 v[224:227], v103 offset:4704
	s_waitcnt lgkmcnt(4)
	v_mfma_f32_32x32x16_bf16 v[0:15], v[252:255], v[216:219], v[0:15]
	s_waitcnt lgkmcnt(3)
	v_mfma_f32_32x32x16_bf16 v[16:31], v[252:255], v[212:215], v[16:31]
	s_waitcnt lgkmcnt(1)
	v_mfma_f32_32x32x16_bf16 v[0:15], v[220:223], v[228:231], v[0:15]
	s_waitcnt lgkmcnt(0)
	v_mfma_f32_32x32x16_bf16 v[16:31], v[220:223], v[224:227], v[16:31]
	s_waitcnt vmcnt(11)
	ds_write_b128 v96, v[36:39] offset:18432
	global_load_dwordx4 v[36:39], v[90:91], off offset:1152
	s_waitcnt vmcnt(11)
	ds_write_b128 v96, v[52:55] offset:23040
	global_load_dwordx4 v[52:55], v[92:93], off offset:1152
	s_waitcnt vmcnt(11)
	ds_write_b128 v96, v[56:59] offset:27648
	global_load_dwordx4 v[56:59], v[94:95], off offset:1152
	s_waitcnt vmcnt(11)
	ds_write_b128 v96, v[60:63] offset:32256
	global_load_dwordx4 v[60:63], v[98:99], off offset:1152
	s_waitcnt vmcnt(11)
	ds_write_b128 v96, v[64:67] offset:55296
	global_load_dwordx4 v[64:67], v[88:89], off offset:1152
	s_waitcnt vmcnt(11)
	ds_write_b128 v96, v[72:75] offset:59904
	global_load_dwordx4 v[72:75], v[100:101], off offset:1152
	s_setprio 0
	s_waitcnt lgkmcnt(0)
	s_barrier
	s_setprio 1
	ds_read_b128 v[212:215], v104 offset:55296
	ds_read_b128 v[216:219], v103 offset:18432
	ds_read_b128 v[220:223], v103 offset:23040
	ds_read_b128 v[224:227], v104 offset:55328
	ds_read_b128 v[228:231], v103 offset:18464
	ds_read_b128 v[244:247], v103 offset:23072
	ds_read_b128 v[252:255], v104 offset:55360
	s_waitcnt lgkmcnt(5)
	v_mfma_f32_32x32x16_bf16 v[0:15], v[212:215], v[216:219], v[0:15]
	ds_read_b128 v[216:219], v103 offset:18496
	s_waitcnt lgkmcnt(5)
	v_mfma_f32_32x32x16_bf16 v[16:31], v[212:215], v[220:223], v[16:31]
	ds_read_b128 v[212:215], v103 offset:23104
	ds_read_b128 v[220:223], v104 offset:55392
	s_waitcnt lgkmcnt(5)
	v_mfma_f32_32x32x16_bf16 v[0:15], v[224:227], v[228:231], v[0:15]
	ds_read_b128 v[228:231], v103 offset:18528
	s_waitcnt lgkmcnt(5)
	v_mfma_f32_32x32x16_bf16 v[16:31], v[224:227], v[244:247], v[16:31]
	ds_read_b128 v[224:227], v103 offset:23136
	s_waitcnt lgkmcnt(4)
	v_mfma_f32_32x32x16_bf16 v[0:15], v[252:255], v[216:219], v[0:15]
	s_waitcnt lgkmcnt(3)
	v_mfma_f32_32x32x16_bf16 v[16:31], v[252:255], v[212:215], v[16:31]
	s_waitcnt lgkmcnt(1)
	v_mfma_f32_32x32x16_bf16 v[0:15], v[220:223], v[228:231], v[0:15]
	s_waitcnt lgkmcnt(0)
	v_mfma_f32_32x32x16_bf16 v[16:31], v[220:223], v[224:227], v[16:31]
	s_waitcnt vmcnt(11)
	ds_write_b128 v96, v[32:35]
	global_load_dwordx4 v[32:35], v[90:91], off offset:1280
	s_waitcnt vmcnt(11)
	ds_write_b128 v96, v[40:43] offset:4608
	global_load_dwordx4 v[40:43], v[92:93], off offset:1280
	s_waitcnt vmcnt(11)
	ds_write_b128 v96, v[44:47] offset:9216
	global_load_dwordx4 v[44:47], v[94:95], off offset:1280
	s_waitcnt vmcnt(11)
	ds_write_b128 v96, v[48:51] offset:13824
	global_load_dwordx4 v[48:51], v[98:99], off offset:1280
	s_waitcnt vmcnt(11)
	ds_write_b128 v96, v[68:71] offset:36864
	global_load_dwordx4 v[68:71], v[88:89], off offset:1280
	s_waitcnt vmcnt(11)
	ds_write_b128 v96, v[76:79] offset:41472
	global_load_dwordx4 v[76:79], v[100:101], off offset:1280
	s_setprio 0
	s_waitcnt lgkmcnt(0)
	s_barrier
	s_setprio 1
	ds_read_b128 v[212:215], v104 offset:36864
	ds_read_b128 v[216:219], v103
	ds_read_b128 v[220:223], v103 offset:4608
	ds_read_b128 v[224:227], v104 offset:36896
	ds_read_b128 v[228:231], v103 offset:32
	ds_read_b128 v[244:247], v103 offset:4640
	ds_read_b128 v[252:255], v104 offset:36928
	s_waitcnt lgkmcnt(5)
	v_mfma_f32_32x32x16_bf16 v[0:15], v[212:215], v[216:219], v[0:15]
	ds_read_b128 v[216:219], v103 offset:64
	s_waitcnt lgkmcnt(5)
	v_mfma_f32_32x32x16_bf16 v[16:31], v[212:215], v[220:223], v[16:31]
	ds_read_b128 v[212:215], v103 offset:4672
	ds_read_b128 v[220:223], v104 offset:36960
	s_waitcnt lgkmcnt(5)
	v_mfma_f32_32x32x16_bf16 v[0:15], v[224:227], v[228:231], v[0:15]
	ds_read_b128 v[228:231], v103 offset:96
	s_waitcnt lgkmcnt(5)
	v_mfma_f32_32x32x16_bf16 v[16:31], v[224:227], v[244:247], v[16:31]
	ds_read_b128 v[224:227], v103 offset:4704
	s_waitcnt lgkmcnt(4)
	v_mfma_f32_32x32x16_bf16 v[0:15], v[252:255], v[216:219], v[0:15]
	s_waitcnt lgkmcnt(3)
	v_mfma_f32_32x32x16_bf16 v[16:31], v[252:255], v[212:215], v[16:31]
	s_waitcnt lgkmcnt(1)
	v_mfma_f32_32x32x16_bf16 v[0:15], v[220:223], v[228:231], v[0:15]
	s_waitcnt lgkmcnt(0)
	v_mfma_f32_32x32x16_bf16 v[16:31], v[220:223], v[224:227], v[16:31]
	s_waitcnt vmcnt(11)
	ds_write_b128 v96, v[36:39] offset:18432
	global_load_dwordx4 v[36:39], v[90:91], off offset:1408
	s_waitcnt vmcnt(11)
	ds_write_b128 v96, v[52:55] offset:23040
	global_load_dwordx4 v[52:55], v[92:93], off offset:1408
	s_waitcnt vmcnt(11)
	ds_write_b128 v96, v[56:59] offset:27648
	global_load_dwordx4 v[56:59], v[94:95], off offset:1408
	s_waitcnt vmcnt(11)
	ds_write_b128 v96, v[60:63] offset:32256
	global_load_dwordx4 v[60:63], v[98:99], off offset:1408
	s_waitcnt vmcnt(11)
	ds_write_b128 v96, v[64:67] offset:55296
	global_load_dwordx4 v[64:67], v[88:89], off offset:1408
	s_waitcnt vmcnt(11)
	ds_write_b128 v96, v[72:75] offset:59904
	global_load_dwordx4 v[72:75], v[100:101], off offset:1408
	s_setprio 0
	s_waitcnt lgkmcnt(0)
	s_barrier
	s_setprio 1
	ds_read_b128 v[212:215], v104 offset:55296
	ds_read_b128 v[216:219], v103 offset:18432
	ds_read_b128 v[220:223], v103 offset:23040
	ds_read_b128 v[224:227], v104 offset:55328
	ds_read_b128 v[228:231], v103 offset:18464
	ds_read_b128 v[244:247], v103 offset:23072
	ds_read_b128 v[252:255], v104 offset:55360
	s_waitcnt lgkmcnt(5)
	v_mfma_f32_32x32x16_bf16 v[0:15], v[212:215], v[216:219], v[0:15]
	ds_read_b128 v[216:219], v103 offset:18496
	s_waitcnt lgkmcnt(5)
	v_mfma_f32_32x32x16_bf16 v[16:31], v[212:215], v[220:223], v[16:31]
	ds_read_b128 v[212:215], v103 offset:23104
	ds_read_b128 v[220:223], v104 offset:55392
	s_waitcnt lgkmcnt(5)
	v_mfma_f32_32x32x16_bf16 v[0:15], v[224:227], v[228:231], v[0:15]
	ds_read_b128 v[228:231], v103 offset:18528
	s_waitcnt lgkmcnt(5)
	v_mfma_f32_32x32x16_bf16 v[16:31], v[224:227], v[244:247], v[16:31]
	ds_read_b128 v[224:227], v103 offset:23136
	s_waitcnt lgkmcnt(4)
	v_mfma_f32_32x32x16_bf16 v[0:15], v[252:255], v[216:219], v[0:15]
	s_waitcnt lgkmcnt(3)
	v_mfma_f32_32x32x16_bf16 v[16:31], v[252:255], v[212:215], v[16:31]
	s_waitcnt lgkmcnt(1)
	v_mfma_f32_32x32x16_bf16 v[0:15], v[220:223], v[228:231], v[0:15]
	s_waitcnt lgkmcnt(0)
	v_mfma_f32_32x32x16_bf16 v[16:31], v[220:223], v[224:227], v[16:31]
	s_waitcnt vmcnt(11)
	ds_write_b128 v96, v[32:35]
	global_load_dwordx4 v[32:35], v[90:91], off offset:1536
	s_waitcnt vmcnt(11)
	ds_write_b128 v96, v[40:43] offset:4608
	global_load_dwordx4 v[40:43], v[92:93], off offset:1536
	s_waitcnt vmcnt(11)
	ds_write_b128 v96, v[44:47] offset:9216
	global_load_dwordx4 v[44:47], v[94:95], off offset:1536
	s_waitcnt vmcnt(11)
	ds_write_b128 v96, v[48:51] offset:13824
	global_load_dwordx4 v[48:51], v[98:99], off offset:1536
	s_waitcnt vmcnt(11)
	ds_write_b128 v96, v[68:71] offset:36864
	global_load_dwordx4 v[68:71], v[88:89], off offset:1536
	s_waitcnt vmcnt(11)
	ds_write_b128 v96, v[76:79] offset:41472
	global_load_dwordx4 v[76:79], v[100:101], off offset:1536
	s_setprio 0
	s_waitcnt lgkmcnt(0)
	s_barrier
	s_setprio 1
	ds_read_b128 v[212:215], v104 offset:36864
	ds_read_b128 v[216:219], v103
	ds_read_b128 v[220:223], v103 offset:4608
	ds_read_b128 v[224:227], v104 offset:36896
	ds_read_b128 v[228:231], v103 offset:32
	ds_read_b128 v[244:247], v103 offset:4640
	ds_read_b128 v[252:255], v104 offset:36928
	s_waitcnt lgkmcnt(5)
	v_mfma_f32_32x32x16_bf16 v[0:15], v[212:215], v[216:219], v[0:15]
	ds_read_b128 v[216:219], v103 offset:64
	s_waitcnt lgkmcnt(5)
	v_mfma_f32_32x32x16_bf16 v[16:31], v[212:215], v[220:223], v[16:31]
	ds_read_b128 v[212:215], v103 offset:4672
	ds_read_b128 v[220:223], v104 offset:36960
	s_waitcnt lgkmcnt(5)
	v_mfma_f32_32x32x16_bf16 v[0:15], v[224:227], v[228:231], v[0:15]
	ds_read_b128 v[228:231], v103 offset:96
	s_waitcnt lgkmcnt(5)
	v_mfma_f32_32x32x16_bf16 v[16:31], v[224:227], v[244:247], v[16:31]
	ds_read_b128 v[224:227], v103 offset:4704
	s_waitcnt lgkmcnt(4)
	v_mfma_f32_32x32x16_bf16 v[0:15], v[252:255], v[216:219], v[0:15]
	s_waitcnt lgkmcnt(3)
	v_mfma_f32_32x32x16_bf16 v[16:31], v[252:255], v[212:215], v[16:31]
	s_waitcnt lgkmcnt(1)
	v_mfma_f32_32x32x16_bf16 v[0:15], v[220:223], v[228:231], v[0:15]
	s_waitcnt lgkmcnt(0)
	v_mfma_f32_32x32x16_bf16 v[16:31], v[220:223], v[224:227], v[16:31]
	s_waitcnt vmcnt(11)
	ds_write_b128 v96, v[36:39] offset:18432
	global_load_dwordx4 v[36:39], v[90:91], off offset:1664
	s_waitcnt vmcnt(11)
	ds_write_b128 v96, v[52:55] offset:23040
	global_load_dwordx4 v[52:55], v[92:93], off offset:1664
	s_waitcnt vmcnt(11)
	ds_write_b128 v96, v[56:59] offset:27648
	global_load_dwordx4 v[56:59], v[94:95], off offset:1664
	s_waitcnt vmcnt(11)
	ds_write_b128 v96, v[60:63] offset:32256
	global_load_dwordx4 v[60:63], v[98:99], off offset:1664
	s_waitcnt vmcnt(11)
	ds_write_b128 v96, v[64:67] offset:55296
	global_load_dwordx4 v[64:67], v[88:89], off offset:1664
	s_waitcnt vmcnt(11)
	ds_write_b128 v96, v[72:75] offset:59904
	global_load_dwordx4 v[72:75], v[100:101], off offset:1664
	s_setprio 0
	s_waitcnt lgkmcnt(0)
	s_barrier
	s_setprio 1
	ds_read_b128 v[212:215], v104 offset:55296
	ds_read_b128 v[216:219], v103 offset:18432
	ds_read_b128 v[220:223], v103 offset:23040
	ds_read_b128 v[224:227], v104 offset:55328
	ds_read_b128 v[228:231], v103 offset:18464
	ds_read_b128 v[244:247], v103 offset:23072
	ds_read_b128 v[252:255], v104 offset:55360
	s_waitcnt lgkmcnt(5)
	v_mfma_f32_32x32x16_bf16 v[0:15], v[212:215], v[216:219], v[0:15]
	ds_read_b128 v[216:219], v103 offset:18496
	s_waitcnt lgkmcnt(5)
	v_mfma_f32_32x32x16_bf16 v[16:31], v[212:215], v[220:223], v[16:31]
	ds_read_b128 v[212:215], v103 offset:23104
	ds_read_b128 v[220:223], v104 offset:55392
	s_waitcnt lgkmcnt(5)
	v_mfma_f32_32x32x16_bf16 v[0:15], v[224:227], v[228:231], v[0:15]
	ds_read_b128 v[228:231], v103 offset:18528
	s_waitcnt lgkmcnt(5)
	v_mfma_f32_32x32x16_bf16 v[16:31], v[224:227], v[244:247], v[16:31]
	ds_read_b128 v[224:227], v103 offset:23136
	s_waitcnt lgkmcnt(4)
	v_mfma_f32_32x32x16_bf16 v[0:15], v[252:255], v[216:219], v[0:15]
	s_waitcnt lgkmcnt(3)
	v_mfma_f32_32x32x16_bf16 v[16:31], v[252:255], v[212:215], v[16:31]
	s_waitcnt lgkmcnt(1)
	v_mfma_f32_32x32x16_bf16 v[0:15], v[220:223], v[228:231], v[0:15]
	s_waitcnt lgkmcnt(0)
	v_mfma_f32_32x32x16_bf16 v[16:31], v[220:223], v[224:227], v[16:31]
	s_waitcnt vmcnt(11)
	ds_write_b128 v96, v[32:35]
	global_load_dwordx4 v[32:35], v[90:91], off offset:1792
	s_waitcnt vmcnt(11)
	ds_write_b128 v96, v[40:43] offset:4608
	global_load_dwordx4 v[40:43], v[92:93], off offset:1792
	s_waitcnt vmcnt(11)
	ds_write_b128 v96, v[44:47] offset:9216
	global_load_dwordx4 v[44:47], v[94:95], off offset:1792
	s_waitcnt vmcnt(11)
	ds_write_b128 v96, v[48:51] offset:13824
	global_load_dwordx4 v[48:51], v[98:99], off offset:1792
	s_waitcnt vmcnt(11)
	ds_write_b128 v96, v[68:71] offset:36864
	global_load_dwordx4 v[68:71], v[88:89], off offset:1792
	s_waitcnt vmcnt(11)
	ds_write_b128 v96, v[76:79] offset:41472
	global_load_dwordx4 v[76:79], v[100:101], off offset:1792
	s_setprio 0
	s_waitcnt lgkmcnt(0)
	s_barrier
	s_setprio 1
	ds_read_b128 v[212:215], v104 offset:36864
	ds_read_b128 v[216:219], v103
	ds_read_b128 v[220:223], v103 offset:4608
	ds_read_b128 v[224:227], v104 offset:36896
	ds_read_b128 v[228:231], v103 offset:32
	ds_read_b128 v[244:247], v103 offset:4640
	ds_read_b128 v[252:255], v104 offset:36928
	s_waitcnt lgkmcnt(5)
	v_mfma_f32_32x32x16_bf16 v[0:15], v[212:215], v[216:219], v[0:15]
	ds_read_b128 v[216:219], v103 offset:64
	s_waitcnt lgkmcnt(5)
	v_mfma_f32_32x32x16_bf16 v[16:31], v[212:215], v[220:223], v[16:31]
	ds_read_b128 v[212:215], v103 offset:4672
	ds_read_b128 v[220:223], v104 offset:36960
	s_waitcnt lgkmcnt(5)
	v_mfma_f32_32x32x16_bf16 v[0:15], v[224:227], v[228:231], v[0:15]
	ds_read_b128 v[228:231], v103 offset:96
	s_waitcnt lgkmcnt(5)
	v_mfma_f32_32x32x16_bf16 v[16:31], v[224:227], v[244:247], v[16:31]
	ds_read_b128 v[224:227], v103 offset:4704
	s_waitcnt lgkmcnt(4)
	v_mfma_f32_32x32x16_bf16 v[0:15], v[252:255], v[216:219], v[0:15]
	s_waitcnt lgkmcnt(3)
	v_mfma_f32_32x32x16_bf16 v[16:31], v[252:255], v[212:215], v[16:31]
	s_waitcnt lgkmcnt(1)
	v_mfma_f32_32x32x16_bf16 v[0:15], v[220:223], v[228:231], v[0:15]
	s_waitcnt lgkmcnt(0)
	v_mfma_f32_32x32x16_bf16 v[16:31], v[220:223], v[224:227], v[16:31]
	s_waitcnt vmcnt(11)
	ds_write_b128 v96, v[36:39] offset:18432
	global_load_dwordx4 v[36:39], v[90:91], off offset:1920
	s_waitcnt vmcnt(11)
	ds_write_b128 v96, v[52:55] offset:23040
	global_load_dwordx4 v[52:55], v[92:93], off offset:1920
	s_waitcnt vmcnt(11)
	ds_write_b128 v96, v[56:59] offset:27648
	global_load_dwordx4 v[56:59], v[94:95], off offset:1920
	s_waitcnt vmcnt(11)
	ds_write_b128 v96, v[60:63] offset:32256
	global_load_dwordx4 v[60:63], v[98:99], off offset:1920
	s_waitcnt vmcnt(11)
	ds_write_b128 v96, v[64:67] offset:55296
	global_load_dwordx4 v[64:67], v[88:89], off offset:1920
	s_waitcnt vmcnt(11)
	ds_write_b128 v96, v[72:75] offset:59904
	global_load_dwordx4 v[72:75], v[100:101], off offset:1920
	s_setprio 0
	s_waitcnt lgkmcnt(0)
	s_barrier
	s_setprio 1
	ds_read_b128 v[212:215], v104 offset:55296
	ds_read_b128 v[216:219], v103 offset:18432
	ds_read_b128 v[220:223], v103 offset:23040
	ds_read_b128 v[224:227], v104 offset:55328
	ds_read_b128 v[228:231], v103 offset:18464
	ds_read_b128 v[244:247], v103 offset:23072
	ds_read_b128 v[252:255], v104 offset:55360
	s_waitcnt lgkmcnt(5)
	v_mfma_f32_32x32x16_bf16 v[0:15], v[212:215], v[216:219], v[0:15]
	ds_read_b128 v[216:219], v103 offset:18496
	s_waitcnt lgkmcnt(5)
	v_mfma_f32_32x32x16_bf16 v[16:31], v[212:215], v[220:223], v[16:31]
	ds_read_b128 v[212:215], v103 offset:23104
	ds_read_b128 v[220:223], v104 offset:55392
	s_waitcnt lgkmcnt(5)
	v_mfma_f32_32x32x16_bf16 v[0:15], v[224:227], v[228:231], v[0:15]
	ds_read_b128 v[228:231], v103 offset:18528
	s_waitcnt lgkmcnt(5)
	v_mfma_f32_32x32x16_bf16 v[16:31], v[224:227], v[244:247], v[16:31]
	ds_read_b128 v[224:227], v103 offset:23136
	s_waitcnt lgkmcnt(4)
	v_mfma_f32_32x32x16_bf16 v[0:15], v[252:255], v[216:219], v[0:15]
	s_waitcnt lgkmcnt(3)
	v_mfma_f32_32x32x16_bf16 v[16:31], v[252:255], v[212:215], v[16:31]
	s_waitcnt lgkmcnt(1)
	v_mfma_f32_32x32x16_bf16 v[0:15], v[220:223], v[228:231], v[0:15]
	s_waitcnt lgkmcnt(0)
	v_mfma_f32_32x32x16_bf16 v[16:31], v[220:223], v[224:227], v[16:31]
	s_waitcnt vmcnt(11)
	ds_write_b128 v96, v[32:35]
	s_waitcnt vmcnt(10)
	ds_write_b128 v96, v[40:43] offset:4608
	s_waitcnt vmcnt(9)
	ds_write_b128 v96, v[44:47] offset:9216
	s_waitcnt vmcnt(8)
	ds_write_b128 v96, v[48:51] offset:13824
	s_waitcnt vmcnt(7)
	ds_write_b128 v96, v[68:71] offset:36864
	s_waitcnt vmcnt(6)
	ds_write_b128 v96, v[76:79] offset:41472
	s_setprio 0
	s_waitcnt lgkmcnt(0)
	s_barrier
	s_setprio 1
	ds_read_b128 v[212:215], v104 offset:36864
	ds_read_b128 v[216:219], v103
	ds_read_b128 v[220:223], v103 offset:4608
	ds_read_b128 v[224:227], v104 offset:36896
	ds_read_b128 v[228:231], v103 offset:32
	ds_read_b128 v[244:247], v103 offset:4640
	ds_read_b128 v[252:255], v104 offset:36928
	s_waitcnt lgkmcnt(5)
	v_mfma_f32_32x32x16_bf16 v[0:15], v[212:215], v[216:219], v[0:15]
	ds_read_b128 v[216:219], v103 offset:64
	s_waitcnt lgkmcnt(5)
	v_mfma_f32_32x32x16_bf16 v[16:31], v[212:215], v[220:223], v[16:31]
	ds_read_b128 v[212:215], v103 offset:4672
	ds_read_b128 v[220:223], v104 offset:36960
	s_waitcnt lgkmcnt(5)
	v_mfma_f32_32x32x16_bf16 v[0:15], v[224:227], v[228:231], v[0:15]
	ds_read_b128 v[228:231], v103 offset:96
	s_waitcnt lgkmcnt(5)
	v_mfma_f32_32x32x16_bf16 v[16:31], v[224:227], v[244:247], v[16:31]
	ds_read_b128 v[224:227], v103 offset:4704
	s_waitcnt lgkmcnt(4)
	v_mfma_f32_32x32x16_bf16 v[0:15], v[252:255], v[216:219], v[0:15]
	s_waitcnt lgkmcnt(3)
	v_mfma_f32_32x32x16_bf16 v[16:31], v[252:255], v[212:215], v[16:31]
	s_waitcnt lgkmcnt(1)
	v_mfma_f32_32x32x16_bf16 v[0:15], v[220:223], v[228:231], v[0:15]
	s_waitcnt lgkmcnt(0)
	v_mfma_f32_32x32x16_bf16 v[16:31], v[220:223], v[224:227], v[16:31]
	s_waitcnt vmcnt(5)
	ds_write_b128 v96, v[36:39] offset:18432
	s_waitcnt vmcnt(4)
	ds_write_b128 v96, v[52:55] offset:23040
	s_waitcnt vmcnt(3)
	ds_write_b128 v96, v[56:59] offset:27648
	s_waitcnt vmcnt(2)
	ds_write_b128 v96, v[60:63] offset:32256
	s_waitcnt vmcnt(1)
	ds_write_b128 v96, v[64:67] offset:55296
	s_waitcnt vmcnt(0)
	ds_write_b128 v96, v[72:75] offset:59904
	s_setprio 0
	s_waitcnt lgkmcnt(0)
	s_barrier
	s_setprio 1
	ds_read_b128 v[212:215], v104 offset:55296
	ds_read_b128 v[216:219], v103 offset:18432
	ds_read_b128 v[220:223], v103 offset:23040
	ds_read_b128 v[224:227], v104 offset:55328
	ds_read_b128 v[228:231], v103 offset:18464
	ds_read_b128 v[244:247], v103 offset:23072
	ds_read_b128 v[252:255], v104 offset:55360
	s_waitcnt lgkmcnt(5)
	v_mfma_f32_32x32x16_bf16 v[0:15], v[212:215], v[216:219], v[0:15]
	ds_read_b128 v[216:219], v103 offset:18496
	s_waitcnt lgkmcnt(5)
	v_mfma_f32_32x32x16_bf16 v[16:31], v[212:215], v[220:223], v[16:31]
	ds_read_b128 v[212:215], v103 offset:23104
	ds_read_b128 v[220:223], v104 offset:55392
	s_waitcnt lgkmcnt(5)
	v_mfma_f32_32x32x16_bf16 v[0:15], v[224:227], v[228:231], v[0:15]
	ds_read_b128 v[228:231], v103 offset:18528
	s_waitcnt lgkmcnt(5)
	v_mfma_f32_32x32x16_bf16 v[16:31], v[224:227], v[244:247], v[16:31]
	ds_read_b128 v[224:227], v103 offset:23136
	s_waitcnt lgkmcnt(4)
	v_mfma_f32_32x32x16_bf16 v[0:15], v[252:255], v[216:219], v[0:15]
	s_waitcnt lgkmcnt(3)
	v_mfma_f32_32x32x16_bf16 v[16:31], v[252:255], v[212:215], v[16:31]
	s_waitcnt lgkmcnt(1)
	v_mfma_f32_32x32x16_bf16 v[0:15], v[220:223], v[228:231], v[0:15]
	s_waitcnt lgkmcnt(0)
	v_mfma_f32_32x32x16_bf16 v[16:31], v[220:223], v[224:227], v[16:31]
	s_setprio 0
	s_lshl_b32 s7, s2, 7
	s_min_i32 s2, s7, 0x4000
	s_ashr_i32 s2, s2, 11
	s_mul_hi_i32 s3, s2, 0x9000
	s_mul_i32 s2, s2, 0x9000
	s_add_u32 s2, s42, s2
	v_add_u32_e32 v32, s7, v169
	s_addc_u32 s3, s43, s3
	v_lshl_or_b32 v44, s6, 6, v102
	v_ashrrev_i32_e32 v33, 31, v32
	s_add_u32 s2, s2, 0x5000
	v_lshlrev_b64 v[34:35], 12, v[32:33]
	v_ashrrev_i32_e32 v45, 31, v44
	v_or_b32_e32 v32, 32, v32
	s_addc_u32 s3, s3, 0
	v_lshlrev_b64 v[36:37], 2, v[44:45]
	v_ashrrev_i32_e32 v33, 31, v32
	v_lshl_add_u64 v[38:39], s[2:3], 0, v[36:37]
	v_lshl_add_u64 v[36:37], s[92:93], 0, v[36:37]
	v_lshlrev_b64 v[32:33], 12, v[32:33]
	s_barrier
	v_lshl_add_u64 v[46:47], v[36:37], 0, v[34:35]
	v_lshl_add_u64 v[48:49], v[36:37], 0, v[32:33]
	global_load_dwordx4 v[32:35], v[38:39], off
	s_nop 0
	global_load_dwordx4 v[36:39], v[46:47], off
	global_load_dwordx4 v[40:43], v[48:49], off
	s_add_i32 s12, s12, s94
	s_cmp_lt_i32 s12, s11
	s_waitcnt vmcnt(1)
	v_pk_fma_f32 v[0:1], v[0:1], v[32:33], v[36:37]
	v_pk_fma_f32 v[2:3], v[2:3], v[34:35], v[38:39]
	global_store_dwordx4 v[46:47], v[0:3], off
	s_waitcnt vmcnt(1)
	v_pk_fma_f32 v[16:17], v[16:17], v[32:33], v[40:41]
	v_pk_fma_f32 v[18:19], v[18:19], v[34:35], v[42:43]
	v_or_b32_e32 v0, 8, v44
	v_ashrrev_i32_e32 v1, 31, v0
	global_store_dwordx4 v[48:49], v[16:19], off
	v_lshl_add_u64 v[0:1], v[0:1], 2, s[2:3]
	global_load_dwordx4 v[0:3], v[0:1], off
	global_load_dwordx4 v[16:19], v[46:47], off offset:32
	global_load_dwordx4 v[32:35], v[48:49], off offset:32
	s_waitcnt vmcnt(1)
	v_pk_fma_f32 v[4:5], v[4:5], v[0:1], v[16:17]
	s_waitcnt vmcnt(0)
	v_pk_fma_f32 v[0:1], v[20:21], v[0:1], v[32:33]
	v_pk_fma_f32 v[6:7], v[6:7], v[2:3], v[18:19]
	v_pk_fma_f32 v[2:3], v[22:23], v[2:3], v[34:35]
	global_store_dwordx4 v[48:49], v[0:3], off offset:32
	global_store_dwordx4 v[46:47], v[4:7], off offset:32
	s_nop 0
	v_or_b32_e32 v0, 16, v44
	v_ashrrev_i32_e32 v1, 31, v0
	v_lshl_add_u64 v[0:1], v[0:1], 2, s[2:3]
	global_load_dwordx4 v[0:3], v[0:1], off
	global_load_dwordx4 v[4:7], v[46:47], off offset:64
	global_load_dwordx4 v[16:19], v[48:49], off offset:64
	s_waitcnt vmcnt(1)
	v_pk_fma_f32 v[4:5], v[8:9], v[0:1], v[4:5]
	s_waitcnt vmcnt(0)
	v_pk_fma_f32 v[0:1], v[24:25], v[0:1], v[16:17]
	v_pk_fma_f32 v[6:7], v[10:11], v[2:3], v[6:7]
	v_pk_fma_f32 v[2:3], v[26:27], v[2:3], v[18:19]
	global_store_dwordx4 v[48:49], v[0:3], off offset:64
	global_store_dwordx4 v[46:47], v[4:7], off offset:64
	s_nop 0
	v_or_b32_e32 v0, 24, v44
	v_ashrrev_i32_e32 v1, 31, v0
	v_lshl_add_u64 v[0:1], v[0:1], 2, s[2:3]
	global_load_dwordx4 v[0:3], v[0:1], off
	global_load_dwordx4 v[4:7], v[46:47], off offset:96
	global_load_dwordx4 v[8:11], v[48:49], off offset:96
	s_waitcnt vmcnt(1)
	v_pk_fma_f32 v[4:5], v[12:13], v[0:1], v[4:5]
	s_waitcnt vmcnt(0)
	v_pk_fma_f32 v[0:1], v[28:29], v[0:1], v[8:9]
	v_pk_fma_f32 v[6:7], v[14:15], v[2:3], v[6:7]
	v_pk_fma_f32 v[2:3], v[30:31], v[2:3], v[10:11]
	global_store_dwordx4 v[46:47], v[4:7], off offset:96
	global_store_dwordx4 v[48:49], v[0:3], off offset:96
	s_cbranch_scc1 .LBB0_1245

.LBB0_1296:
	v_min_i32_e32 v0, 0x4000, v12
	v_ashrrev_i32_e32 v0, 11, v0
	v_mul_hi_i32_i24_e32 v1, 0x9000, v0
	v_mul_i32_i24_e32 v0, 0x9000, v0
	v_lshl_add_u64 v[0:1], s[6:7], 0, v[0:1]
	v_lshl_add_u64 v[26:27], v[0:1], 0, s[16:17]
	v_lshl_add_u64 v[58:59], s[92:93], 0, v[20:21]
	v_lshl_add_u64 v[4:5], v[26:27], 0, v[96:97]
	v_lshl_add_u64 v[24:25], v[0:1], 0, v[96:97]
	global_load_dwordx4 v[38:41], v[58:59], off offset:16
	global_load_dwordx4 v[8:11], v[58:59], off
	global_load_dwordx4 v[42:45], v[16:17], off offset:16
	global_load_dwordx4 v[46:49], v[16:17], off
	global_load_dwordx4 v[50:53], v[24:25], off offset:16
	global_load_dwordx4 v[54:57], v[24:25], off
	global_load_dwordx4 v[0:3], v[4:5], off offset:16
	global_load_dwordx4 v[4:7], v[4:5], off
	v_mov_b32_e32 v23, v97
	v_lshl_add_u64 v[26:27], v[26:27], 0, v[22:23]
	v_lshl_add_u64 v[30:31], s[92:93], 0, v[18:19]
	v_add_u32_e32 v12, s8, v12
	v_lshl_add_u64 v[18:19], v[18:19], 0, s[30:31]
	v_lshl_add_u64 v[20:21], v[20:21], 0, s[14:15]
	s_waitcnt vmcnt(7)
	v_mov_b32_e32 v67, v39
	s_waitcnt vmcnt(6)
	v_mov_b32_e32 v66, v9
	v_pk_mul_f32 v[66:67], v[66:67], v[66:67]
	s_waitcnt vmcnt(1)
	v_pk_add_f32 v[60:61], v[0:1], 1.0 op_sel_hi:[1,0]
	s_waitcnt vmcnt(0)
	v_pk_add_f32 v[62:63], v[6:7], 1.0 op_sel_hi:[1,0]
	v_mov_b32_e32 v6, v8
	v_mov_b32_e32 v7, v38
	v_mov_b32_e32 v0, v10
	v_mov_b32_e32 v1, v40
	v_pk_fma_f32 v[6:7], v[6:7], v[6:7], v[66:67]
	v_pk_add_f32 v[64:65], v[4:5], 1.0 op_sel_hi:[1,0]
	v_mov_b32_e32 v4, v11
	v_mov_b32_e32 v5, v41
	v_pk_fma_f32 v[0:1], v[0:1], v[0:1], v[6:7]
	v_pk_add_f32 v[68:69], v[2:3], 1.0 op_sel_hi:[1,0]
	v_pk_fma_f32 v[66:67], v[4:5], v[4:5], v[0:1]
	global_load_dwordx4 v[0:3], v[58:59], off offset:2064
	global_load_dwordx4 v[4:7], v[58:59], off offset:2048
	global_load_dwordx4 v[86:89], v[14:15], off offset:16
	global_load_dwordx4 v[90:93], v[14:15], off
	global_load_dwordx4 v[98:101], v[24:25], off offset:2064
	global_load_dwordx4 v[106:109], v[24:25], off offset:2048
	global_load_dwordx4 v[110:113], v[26:27], off offset:16
	global_load_dwordx4 v[114:117], v[26:27], off
	v_add_f32_e32 v13, v66, v67
	s_waitcnt vmcnt(7)
	v_mov_b32_e32 v75, v1
	s_waitcnt vmcnt(6)
	v_mov_b32_e32 v74, v5
	v_mov_b32_e32 v72, v4
	v_mov_b32_e32 v73, v0
	v_pk_mul_f32 v[74:75], v[74:75], v[74:75]
	v_mov_b32_e32 v58, v6
	v_mov_b32_e32 v59, v2
	v_pk_fma_f32 v[72:73], v[72:73], v[72:73], v[74:75]
	v_mov_b32_e32 v70, v7
	v_mov_b32_e32 v71, v3
	v_pk_fma_f32 v[58:59], v[58:59], v[58:59], v[72:73]
	v_pk_fma_f32 v[58:59], v[70:71], v[70:71], v[58:59]
	v_add_f32_e32 v13, v13, v58
	v_add_f32_e32 v13, v13, v59
	v_mov_b32_e32 v23, v13
	v_mov_b32_e32 v255, v13
	s_nop 1
	v_permlane32_swap_b32_e32 v23, v255
	s_waitcnt lgkmcnt(0)
	v_add_f32_e32 v13, v23, v255
	v_mov_b32_e32 v23, v13
	v_mov_b32_e32 v255, v13
	s_nop 1
	v_permlane16_swap_b32_e32 v23, v255
	s_nop 1
	v_mov_b32_dpp v23, v255 quad_perm:[0,1,2,3] row_mask:0x5 bank_mask:0xf
	s_nop 0
	v_add_f32_e32 v13, v13, v23
	s_nop 1
	v_mov_b32_dpp v23, v13 row_ror:8 row_mask:0xf bank_mask:0xf
	s_nop 0
	v_add_f32_e32 v13, v13, v23
	s_nop 1
	v_mov_b32_dpp v23, v13 row_shl:4 row_mask:0xf bank_mask:0x5
	v_mov_b32_dpp v23, v13 row_shr:4 row_mask:0xf bank_mask:0xa
	s_nop 0
	v_add_f32_e32 v13, v13, v23
	s_nop 1
	v_mov_b32_dpp v23, v13 quad_perm:[2,3,0,1] row_mask:0xf bank_mask:0xf
	v_add_f32_e32 v13, v13, v23
	s_nop 1
	v_add_f32_dpp v13, v13, v13 quad_perm:[1,0,3,2] row_mask:0xf bank_mask:0xf
	v_fmamk_f32 v13, v13, 0x3a800000, v163
	v_cmp_gt_f32_e32 vcc, s86, v13
	v_mul_f32_e32 v23, 0x4b800000, v13
	s_nop 0
	v_cndmask_b32_e32 v13, v13, v23, vcc
	v_rsq_f32_e32 v13, v13
	s_nop 0
	v_mul_f32_e32 v23, 0x45800000, v13
	v_cndmask_b32_e32 v28, v13, v23, vcc
	v_pk_mul_f32 v[8:9], v[8:9], v[28:29] op_sel_hi:[1,0]
	v_pk_mul_f32 v[10:11], v[10:11], v[28:29] op_sel_hi:[1,0]
	v_pk_mul_f32 v[8:9], v[46:47], v[8:9]
	v_pk_mul_f32 v[10:11], v[48:49], v[10:11]
	v_pk_fma_f32 v[8:9], v[64:65], v[8:9], v[54:55]
	v_pk_fma_f32 v[10:11], v[62:63], v[10:11], v[56:57]
	v_cvt_pk_bf16_f32 v8, v8, v9
	v_cvt_pk_bf16_f32 v9, v10, v11
	v_pk_mul_f32 v[10:11], v[38:39], v[28:29] op_sel_hi:[1,0]
	v_pk_mul_f32 v[38:39], v[40:41], v[28:29] op_sel_hi:[1,0]
	v_pk_mul_f32 v[10:11], v[10:11], v[42:43]
	v_pk_mul_f32 v[38:39], v[38:39], v[44:45]
	v_pk_fma_f32 v[10:11], v[10:11], v[60:61], v[50:51]
	v_pk_fma_f32 v[38:39], v[38:39], v[68:69], v[52:53]
	v_add_co_u32_e32 v30, vcc, s28, v30
	v_cvt_pk_bf16_f32 v10, v10, v11
	v_cvt_pk_bf16_f32 v11, v38, v39
	v_addc_co_u32_e32 v31, vcc, 0, v31, vcc
	global_store_dwordx4 v[30:31], v[8:11], off
	v_pk_mul_f32 v[4:5], v[4:5], v[28:29] op_sel_hi:[1,0]
	v_pk_mul_f32 v[6:7], v[6:7], v[28:29] op_sel_hi:[1,0]
	v_pk_mul_f32 v[0:1], v[0:1], v[28:29] op_sel_hi:[1,0]
	v_pk_mul_f32 v[2:3], v[2:3], v[28:29] op_sel_hi:[1,0]
	v_cmp_le_i32_e32 vcc, s38, v12
	s_or_b64 s[12:13], vcc, s[12:13]
	s_waitcnt vmcnt(6)
	v_pk_mul_f32 v[0:1], v[0:1], v[86:87]
	s_waitcnt vmcnt(5)
	v_pk_mul_f32 v[4:5], v[4:5], v[90:91]
	v_pk_mul_f32 v[6:7], v[6:7], v[92:93]
	v_pk_mul_f32 v[2:3], v[2:3], v[88:89]
	s_waitcnt vmcnt(1)
	v_pk_add_f32 v[24:25], v[114:115], 1.0 op_sel_hi:[1,0]
	v_pk_fma_f32 v[4:5], v[4:5], v[24:25], v[106:107]
	v_pk_add_f32 v[24:25], v[116:117], 1.0 op_sel_hi:[1,0]
	v_cvt_pk_bf16_f32 v4, v4, v5
	v_pk_fma_f32 v[6:7], v[6:7], v[24:25], v[108:109]
	v_cvt_pk_bf16_f32 v5, v6, v7
	v_pk_add_f32 v[6:7], v[110:111], 1.0 op_sel_hi:[1,0]
	v_pk_fma_f32 v[0:1], v[0:1], v[6:7], v[98:99]
	v_pk_add_f32 v[6:7], v[112:113], 1.0 op_sel_hi:[1,0]
	v_pk_fma_f32 v[2:3], v[2:3], v[6:7], v[100:101]
	v_cvt_pk_bf16_f32 v6, v0, v1
	v_cvt_pk_bf16_f32 v7, v2, v3
	global_store_dwordx4 v[30:31], v[4:7], off offset:1024
	s_andn2_b64 exec, exec, s[12:13]
	s_cbranch_execnz .LBB0_1296

.LBB0_1348:
	s_nop 2
	v_mul_f32_e32 v133, 0xbfb8aa3b, v32
	v_exp_f32_e32 v133, v133
	v_and_b32_e32 v98, 64, v196
	v_xor_b32_e32 v96, 32, v196
	v_add_u32_e32 v98, 64, v98
	v_add_f32_e32 v133, 1.0, v133
	v_rcp_f32_e32 v138, v133
	v_mul_f32_e32 v133, 0xbfb8aa3b, v33
	v_exp_f32_e32 v133, v133
	v_cmp_lt_i32_e32 vcc, v96, v98
	v_lshl_or_b32 v134, s6, 6, v174
	v_lshl_add_u32 v132, s12, 7, v169
	v_add_f32_e32 v133, 1.0, v133
	v_rcp_f32_e32 v139, v133
	v_cndmask_b32_e32 v96, v196, v96, vcc
	v_lshlrev_b32_e32 v96, 2, v96
	v_mov_b64_e32 v[98:99], s[56:57]
	v_pk_mul_f32 v[32:33], v[32:33], v[138:139]
	v_ashrrev_i32_e32 v135, 31, v134
	v_pk_mul_f32 v[32:33], v[48:49], v[32:33]
	v_mul_f32_e32 v48, 0xbfb8aa3b, v34
	v_mul_f32_e32 v49, 0xbfb8aa3b, v35
	v_exp_f32_e32 v48, v48
	v_exp_f32_e32 v49, v49
	v_mad_i64_i32 v[136:137], s[6:7], v132, s18, v[98:99]
	v_add_f32_e32 v48, 1.0, v48
	v_add_f32_e32 v49, 1.0, v49
	v_rcp_f32_e32 v48, v48
	v_rcp_f32_e32 v49, v49
	s_waitcnt lgkmcnt(0)
	s_barrier
	v_pk_mul_f32 v[34:35], v[34:35], v[48:49]
	v_cvt_pk_bf16_f32 v48, v32, v33
	v_pk_mul_f32 v[34:35], v[50:51], v[34:35]
	v_mul_f32_e32 v32, 0xbfb8aa3b, v36
	v_cvt_pk_bf16_f32 v49, v34, v35
	v_mul_f32_e32 v33, 0xbfb8aa3b, v37
	v_mul_f32_e32 v34, 0xbfb8aa3b, v38
	v_mul_f32_e32 v35, 0xbfb8aa3b, v39
	v_exp_f32_e32 v32, v32
	v_exp_f32_e32 v33, v33
	v_exp_f32_e32 v34, v34
	v_exp_f32_e32 v35, v35
	v_add_f32_e32 v32, 1.0, v32
	v_add_f32_e32 v33, 1.0, v33
	v_add_f32_e32 v34, 1.0, v34
	v_add_f32_e32 v35, 1.0, v35
	v_rcp_f32_e32 v32, v32
	v_rcp_f32_e32 v33, v33
	v_rcp_f32_e32 v34, v34
	v_rcp_f32_e32 v35, v35
	s_mov_b64 s[48:49], 0
	v_pk_mul_f32 v[32:33], v[36:37], v[32:33]
	s_andn2_b64 vcc, exec, s[2:3]
	v_pk_mul_f32 v[34:35], v[38:39], v[34:35]
	v_pk_mul_f32 v[32:33], v[52:53], v[32:33]
	v_pk_mul_f32 v[34:35], v[54:55], v[34:35]
	v_cvt_pk_bf16_f32 v32, v32, v33
	v_cvt_pk_bf16_f32 v33, v34, v35
	v_cndmask_b32_e64 v34, v48, v32, s[38:39]
	v_cndmask_b32_e64 v35, v49, v33, s[38:39]
	v_mov_b32_e32 v255, v34
	s_nop 1
	v_permlane32_swap_b32_e32 v34, v255
	s_nop 1
	v_mov_b32_dpp v34, v255 quad_perm:[0,1,2,3] row_mask:0x3 bank_mask:0xf
	v_mov_b32_e32 v255, v35
	s_nop 1
	v_permlane32_swap_b32_e32 v35, v255
	s_nop 1
	v_mov_b32_dpp v35, v255 quad_perm:[0,1,2,3] row_mask:0x3 bank_mask:0xf
	v_cndmask_b32_e64 v38, v32, v34, s[38:39]
	v_cndmask_b32_e64 v39, v33, v35, s[38:39]
	v_lshlrev_b64 v[32:33], 1, v[134:135]
	v_cndmask_b32_e64 v37, v35, v49, s[38:39]
	v_cndmask_b32_e64 v36, v34, v48, s[38:39]
	v_lshl_add_u64 v[34:35], v[136:137], 0, v[32:33]
	global_store_dwordx4 v[34:35], v[36:39], off
	s_nop 1
	v_mul_f32_e32 v36, 0xbfb8aa3b, v40
	v_mul_f32_e32 v37, 0xbfb8aa3b, v41
	v_mul_f32_e32 v38, 0xbfb8aa3b, v42
	v_mul_f32_e32 v39, 0xbfb8aa3b, v43
	v_exp_f32_e32 v36, v36
	v_exp_f32_e32 v37, v37
	v_exp_f32_e32 v38, v38
	v_exp_f32_e32 v39, v39
	v_add_f32_e32 v36, 1.0, v36
	v_add_f32_e32 v37, 1.0, v37
	v_add_f32_e32 v38, 1.0, v38
	v_add_f32_e32 v39, 1.0, v39
	v_rcp_f32_e32 v36, v36
	v_rcp_f32_e32 v37, v37
	v_rcp_f32_e32 v38, v38
	v_rcp_f32_e32 v39, v39
	v_pk_mul_f32 v[36:37], v[40:41], v[36:37]
	v_pk_mul_f32 v[36:37], v[56:57], v[36:37]
	v_pk_mul_f32 v[38:39], v[42:43], v[38:39]
	v_cvt_pk_bf16_f32 v40, v36, v37
	v_pk_mul_f32 v[38:39], v[58:59], v[38:39]
	v_mul_f32_e32 v36, 0xbfb8aa3b, v44
	v_cvt_pk_bf16_f32 v41, v38, v39
	v_mul_f32_e32 v37, 0xbfb8aa3b, v45
	v_mul_f32_e32 v38, 0xbfb8aa3b, v46
	v_mul_f32_e32 v39, 0xbfb8aa3b, v47
	v_exp_f32_e32 v36, v36
	v_exp_f32_e32 v37, v37
	v_exp_f32_e32 v38, v38
	v_exp_f32_e32 v39, v39
	v_add_f32_e32 v36, 1.0, v36
	v_add_f32_e32 v37, 1.0, v37
	v_add_f32_e32 v38, 1.0, v38
	v_add_f32_e32 v39, 1.0, v39
	v_rcp_f32_e32 v36, v36
	v_rcp_f32_e32 v37, v37
	v_rcp_f32_e32 v38, v38
	v_rcp_f32_e32 v39, v39
	v_pk_mul_f32 v[36:37], v[44:45], v[36:37]
	v_pk_mul_f32 v[36:37], v[60:61], v[36:37]
	v_pk_mul_f32 v[38:39], v[46:47], v[38:39]
	v_cvt_pk_bf16_f32 v36, v36, v37
	v_pk_mul_f32 v[38:39], v[62:63], v[38:39]
	v_cvt_pk_bf16_f32 v37, v38, v39
	v_cndmask_b32_e64 v38, v40, v36, s[38:39]
	v_cndmask_b32_e64 v39, v41, v37, s[38:39]
	v_mov_b32_e32 v42, v38
	v_mov_b32_e32 v255, v38
	s_nop 1
	v_permlane32_swap_b32_e32 v42, v255
	s_nop 1
	v_mov_b32_dpp v42, v255 quad_perm:[0,1,2,3] row_mask:0x3 bank_mask:0xf
	v_mov_b32_e32 v43, v39
	v_mov_b32_e32 v255, v39
	s_nop 1
	v_permlane32_swap_b32_e32 v43, v255
	s_nop 1
	v_mov_b32_dpp v43, v255 quad_perm:[0,1,2,3] row_mask:0x3 bank_mask:0xf
	v_cndmask_b32_e64 v38, v36, v42, s[38:39]
	v_cndmask_b32_e64 v39, v37, v43, s[38:39]
	v_cndmask_b32_e64 v37, v43, v41, s[38:39]
	v_cndmask_b32_e64 v36, v42, v40, s[38:39]
	global_store_dwordx4 v[34:35], v[36:39], off offset:32
	v_or_b32_e32 v34, 32, v132
	v_mad_i64_i32 v[34:35], s[6:7], v34, s18, v[98:99]
	v_mul_f32_e32 v36, 0xbfb8aa3b, v0
	v_mul_f32_e32 v37, 0xbfb8aa3b, v1
	v_exp_f32_e32 v36, v36
	v_exp_f32_e32 v37, v37
	s_mov_b32 s7, s51
	v_add_f32_e32 v36, 1.0, v36
	v_add_f32_e32 v37, 1.0, v37
	v_rcp_f32_e32 v36, v36
	v_rcp_f32_e32 v37, v37
	s_nop 0
	v_pk_mul_f32 v[0:1], v[0:1], v[36:37]
	v_pk_mul_f32 v[0:1], v[16:17], v[0:1]
	v_mul_f32_e32 v16, 0xbfb8aa3b, v2
	v_mul_f32_e32 v17, 0xbfb8aa3b, v3
	v_exp_f32_e32 v16, v16
	v_exp_f32_e32 v17, v17
	v_add_f32_e32 v16, 1.0, v16
	v_add_f32_e32 v17, 1.0, v17
	v_rcp_f32_e32 v16, v16
	v_rcp_f32_e32 v17, v17
	s_nop 0
	v_pk_mul_f32 v[2:3], v[2:3], v[16:17]
	v_pk_mul_f32 v[2:3], v[18:19], v[2:3]
	v_cvt_pk_bf16_f32 v16, v0, v1
	v_cvt_pk_bf16_f32 v17, v2, v3
	v_mul_f32_e32 v0, 0xbfb8aa3b, v4
	v_mul_f32_e32 v1, 0xbfb8aa3b, v5
	v_mul_f32_e32 v2, 0xbfb8aa3b, v6
	v_mul_f32_e32 v3, 0xbfb8aa3b, v7
	v_exp_f32_e32 v0, v0
	v_exp_f32_e32 v1, v1
	v_exp_f32_e32 v2, v2
	v_exp_f32_e32 v3, v3
	v_add_f32_e32 v0, 1.0, v0
	v_add_f32_e32 v1, 1.0, v1
	v_add_f32_e32 v2, 1.0, v2
	v_add_f32_e32 v3, 1.0, v3
	v_rcp_f32_e32 v0, v0
	v_rcp_f32_e32 v1, v1
	v_rcp_f32_e32 v2, v2
	v_rcp_f32_e32 v3, v3
	v_pk_mul_f32 v[0:1], v[4:5], v[0:1]
	v_pk_mul_f32 v[0:1], v[20:21], v[0:1]
	v_pk_mul_f32 v[2:3], v[6:7], v[2:3]
	v_cvt_pk_bf16_f32 v0, v0, v1
	v_pk_mul_f32 v[2:3], v[22:23], v[2:3]
	v_cvt_pk_bf16_f32 v1, v2, v3
	v_cndmask_b32_e64 v2, v16, v0, s[38:39]
	v_cndmask_b32_e64 v3, v17, v1, s[38:39]
	v_mov_b32_e32 v255, v2
	s_nop 1
	v_permlane32_swap_b32_e32 v2, v255
	s_nop 1
	v_mov_b32_dpp v2, v255 quad_perm:[0,1,2,3] row_mask:0x3 bank_mask:0xf
	v_mov_b32_e32 v255, v3
	s_nop 1
	v_permlane32_swap_b32_e32 v3, v255
	s_nop 1
	v_mov_b32_dpp v3, v255 quad_perm:[0,1,2,3] row_mask:0x3 bank_mask:0xf
	v_cndmask_b32_e64 v4, v0, v2, s[38:39]
	v_cndmask_b32_e64 v5, v1, v3, s[38:39]
	v_cndmask_b32_e64 v3, v3, v17, s[38:39]
	v_cndmask_b32_e64 v2, v2, v16, s[38:39]
	v_lshl_add_u64 v[0:1], v[34:35], 0, v[32:33]
	global_store_dwordx4 v[0:1], v[2:5], off
	s_nop 1
	v_mul_f32_e32 v2, 0xbfb8aa3b, v8
	v_mul_f32_e32 v3, 0xbfb8aa3b, v9
	v_mul_f32_e32 v4, 0xbfb8aa3b, v10
	v_mul_f32_e32 v5, 0xbfb8aa3b, v11
	v_exp_f32_e32 v2, v2
	v_exp_f32_e32 v3, v3
	v_exp_f32_e32 v4, v4
	v_exp_f32_e32 v5, v5
	v_add_f32_e32 v2, 1.0, v2
	v_add_f32_e32 v3, 1.0, v3
	v_add_f32_e32 v4, 1.0, v4
	v_add_f32_e32 v5, 1.0, v5
	v_rcp_f32_e32 v2, v2
	v_rcp_f32_e32 v3, v3
	v_rcp_f32_e32 v4, v4
	v_rcp_f32_e32 v5, v5
	v_pk_mul_f32 v[2:3], v[8:9], v[2:3]
	v_pk_mul_f32 v[2:3], v[24:25], v[2:3]
	v_pk_mul_f32 v[4:5], v[10:11], v[4:5]
	v_cvt_pk_bf16_f32 v6, v2, v3
	v_pk_mul_f32 v[4:5], v[26:27], v[4:5]
	v_mul_f32_e32 v2, 0xbfb8aa3b, v12
	v_cvt_pk_bf16_f32 v7, v4, v5
	v_mul_f32_e32 v3, 0xbfb8aa3b, v13
	v_mul_f32_e32 v4, 0xbfb8aa3b, v14
	v_mul_f32_e32 v5, 0xbfb8aa3b, v15
	v_exp_f32_e32 v2, v2
	v_exp_f32_e32 v3, v3
	v_exp_f32_e32 v4, v4
	v_exp_f32_e32 v5, v5
	v_add_f32_e32 v2, 1.0, v2
	v_add_f32_e32 v3, 1.0, v3
	v_add_f32_e32 v4, 1.0, v4
	v_add_f32_e32 v5, 1.0, v5
	v_rcp_f32_e32 v2, v2
	v_rcp_f32_e32 v3, v3
	v_rcp_f32_e32 v4, v4
	v_rcp_f32_e32 v5, v5
	v_pk_mul_f32 v[2:3], v[12:13], v[2:3]
	v_pk_mul_f32 v[2:3], v[28:29], v[2:3]
	v_pk_mul_f32 v[4:5], v[14:15], v[4:5]
	v_cvt_pk_bf16_f32 v2, v2, v3
	v_pk_mul_f32 v[4:5], v[30:31], v[4:5]
	v_cvt_pk_bf16_f32 v3, v4, v5
	v_cndmask_b32_e64 v4, v6, v2, s[38:39]
	v_cndmask_b32_e64 v5, v7, v3, s[38:39]
	v_mov_b32_e32 v8, v4
	v_mov_b32_e32 v255, v4
	s_nop 1
	v_permlane32_swap_b32_e32 v8, v255
	s_nop 1
	v_mov_b32_dpp v8, v255 quad_perm:[0,1,2,3] row_mask:0x3 bank_mask:0xf
	v_mov_b32_e32 v9, v5
	v_mov_b32_e32 v255, v5
	s_nop 1
	v_permlane32_swap_b32_e32 v9, v255
	s_nop 1
	v_mov_b32_dpp v9, v255 quad_perm:[0,1,2,3] row_mask:0x3 bank_mask:0xf
	v_cndmask_b32_e64 v4, v2, v8, s[38:39]
	v_cndmask_b32_e64 v5, v3, v9, s[38:39]
	v_cndmask_b32_e64 v3, v9, v7, s[38:39]
	v_cndmask_b32_e64 v2, v8, v6, s[38:39]
	global_store_dwordx4 v[0:1], v[2:5], off offset:32
	s_cbranch_vccz .LBB0_1359

.LBB0_1353:
	v_readlane_b32 s42, v248, 8
	v_readlane_b32 s43, v248, 9
	s_add_u32 s7, s42, s40
	s_addc_u32 s13, s43, s41
	s_and_b64 s[40:41], s[44:45], exec
	s_cselect_b32 s40, s7, 0
	v_readlane_b32 s7, v249, 33
	s_cselect_b32 s41, s13, 0
	s_add_u32 s7, s7, s46
	v_readlane_b32 s8, v249, 34
	s_addc_u32 s13, s8, s47
	s_and_b64 s[46:47], s[44:45], exec
	s_cselect_b32 s47, s13, 0
	s_cselect_b32 s46, s7, 0
	v_lshl_add_u64 v[4:5], s[40:41], 0, v[0:1]
	v_lshl_add_u64 v[0:1], s[46:47], 0, v[0:1]
	v_lshl_add_u64 v[146:147], v[0:1], 0, v[96:97]
	v_lshrrev_b32_e32 v0, 1, v2
	v_and_b32_e32 v1, 31, v2
	v_and_or_b32 v1, v0, s81, v1
	v_lshrrev_b32_e32 v0, 2, v2
	v_and_b32_e32 v0, 8, v0
	v_lshl_add_u64 v[148:149], v[4:5], 0, v[96:97]
	v_mad_u64_u32 v[4:5], s[40:41], v1, s84, v[0:1]
	v_and_b32_e32 v1, 0x5f, v2
	v_mad_u32_u24 v0, v1, s84, v0
	v_lshl_add_u32 v176, v4, 1, 0
	v_lshl_add_u32 v96, v0, 1, 0
	v_add_u32_e32 v177, 0xd800, v175
	s_setprio 1
	ds_read_b128 v[212:215], v96 offset:36864
	ds_read_b128 v[216:219], v176
	ds_read_b128 v[220:223], v176 offset:4608
	ds_read_b128 v[224:227], v96 offset:36896
	ds_read_b128 v[228:231], v176 offset:32
	ds_read_b128 v[244:247], v176 offset:4640
	ds_read_b128 v[252:255], v96 offset:41472
	s_waitcnt lgkmcnt(5)
	v_mfma_f32_32x32x16_bf16 v[32:47], v[212:215], v[216:219], 0
	s_waitcnt lgkmcnt(4)
	v_mfma_f32_32x32x16_bf16 v[0:15], v[212:215], v[220:223], 0
	ds_read_b128 v[212:215], v96 offset:41504
	s_waitcnt lgkmcnt(3)
	v_mfma_f32_32x32x16_bf16 v[32:47], v[224:227], v[228:231], v[32:47]
	s_waitcnt lgkmcnt(2)
	v_mfma_f32_32x32x16_bf16 v[0:15], v[224:227], v[244:247], v[0:15]
	ds_read_b128 v[224:227], v96 offset:36928
	s_waitcnt lgkmcnt(2)
	v_mfma_f32_32x32x16_bf16 v[48:63], v[252:255], v[216:219], 0
	ds_read_b128 v[216:219], v176 offset:64
	v_mfma_f32_32x32x16_bf16 v[16:31], v[252:255], v[220:223], 0
	ds_read_b128 v[252:255], v176 offset:4672
	ds_read_b128 v[220:223], v96 offset:41536
	s_waitcnt lgkmcnt(4)
	v_mfma_f32_32x32x16_bf16 v[48:63], v[212:215], v[228:231], v[48:63]
	ds_read_b128 v[228:231], v96 offset:36960
	v_mfma_f32_32x32x16_bf16 v[16:31], v[212:215], v[244:247], v[16:31]
	ds_read_b128 v[212:215], v176 offset:96
	ds_read_b128 v[244:247], v176 offset:4704
	s_waitcnt lgkmcnt(5)
	v_mfma_f32_32x32x16_bf16 v[32:47], v[224:227], v[216:219], v[32:47]
	v_add_co_u32_e32 v154, vcc, s9, v152
	s_waitcnt vmcnt(11)
	ds_write_b128 v175, v[100:103] offset:18432
	s_waitcnt vmcnt(10)
	ds_write_b128 v175, v[104:107] offset:23040
	s_waitcnt lgkmcnt(6)
	v_mfma_f32_32x32x16_bf16 v[0:15], v[224:227], v[252:255], v[0:15]
	ds_read_b128 v[224:227], v96 offset:41568
	s_waitcnt vmcnt(9)
	ds_write_b128 v175, v[108:111] offset:27648
	s_waitcnt vmcnt(8)
	ds_write_b128 v175, v[112:115] offset:32256
	s_waitcnt vmcnt(7)
	s_waitcnt lgkmcnt(8)
	v_mfma_f32_32x32x16_bf16 v[48:63], v[220:223], v[216:219], v[48:63]
	ds_write_b128 v175, v[116:119] offset:55296
	s_waitcnt vmcnt(6)
	ds_write_b128 v175, v[124:127] offset:59904
	s_waitcnt vmcnt(5)
	ds_write_b128 v175, v[120:123] offset:64512
	v_mfma_f32_32x32x16_bf16 v[16:31], v[220:223], v[252:255], v[16:31]
	s_waitcnt vmcnt(4)
	ds_write_b128 v177, v[128:131] offset:13824
	v_addc_co_u32_e32 v155, vcc, 0, v153, vcc
	v_add_co_u32_e32 v156, vcc, s16, v152
	s_waitcnt lgkmcnt(10)
	v_mfma_f32_32x32x16_bf16 v[32:47], v[228:231], v[212:215], v[32:47]
	global_load_dwordx4 v[98:101], v[152:153], off offset:384
	global_load_dwordx4 v[102:105], v[154:155], off offset:384
	v_addc_co_u32_e32 v157, vcc, 0, v153, vcc
	v_add_co_u32_e32 v158, vcc, s17, v152
	global_load_dwordx4 v[106:109], v[156:157], off offset:384
	s_waitcnt lgkmcnt(9)
	v_mfma_f32_32x32x16_bf16 v[0:15], v[228:231], v[244:247], v[0:15]
	s_nop 0
	v_addc_co_u32_e32 v159, vcc, 0, v153, vcc
	v_add_co_u32_e32 v160, vcc, s9, v150
	global_load_dwordx4 v[110:113], v[158:159], off offset:384
	global_load_dwordx4 v[114:117], v[150:151], off offset:384
	s_waitcnt lgkmcnt(6)
	v_mfma_f32_32x32x16_bf16 v[48:63], v[224:227], v[212:215], v[48:63]
	v_addc_co_u32_e32 v161, vcc, 0, v151, vcc
	v_add_co_u32_e32 v170, vcc, s16, v150
	global_load_dwordx4 v[118:121], v[160:161], off offset:384
	s_nop 0
	v_addc_co_u32_e32 v171, vcc, 0, v151, vcc
	v_mfma_f32_32x32x16_bf16 v[16:31], v[224:227], v[244:247], v[16:31]
	v_add_co_u32_e32 v172, vcc, s17, v150
	global_load_dwordx4 v[122:125], v[170:171], off offset:384
	s_nop 0
	v_addc_co_u32_e32 v173, vcc, 0, v151, vcc
	global_load_dwordx4 v[130:133], v[172:173], off offset:384
	s_setprio 0
	s_waitcnt lgkmcnt(0)
	s_barrier
	s_setprio 1
	ds_read_b128 v[212:215], v96 offset:55296
	ds_read_b128 v[216:219], v176 offset:18432
	ds_read_b128 v[220:223], v176 offset:23040
	ds_read_b128 v[224:227], v96 offset:59904
	ds_read_b128 v[228:231], v96 offset:55328
	ds_read_b128 v[244:247], v176 offset:18464
	ds_read_b128 v[252:255], v176 offset:23072
	s_waitcnt lgkmcnt(5)
	v_mfma_f32_32x32x16_bf16 v[32:47], v[212:215], v[216:219], v[32:47]
	s_waitcnt lgkmcnt(4)
	v_mfma_f32_32x32x16_bf16 v[0:15], v[212:215], v[220:223], v[0:15]
	ds_read_b128 v[212:215], v96 offset:59936
	s_waitcnt lgkmcnt(4)
	v_mfma_f32_32x32x16_bf16 v[48:63], v[224:227], v[216:219], v[48:63]
	ds_read_b128 v[216:219], v96 offset:55360
	v_mfma_f32_32x32x16_bf16 v[16:31], v[224:227], v[220:223], v[16:31]
	ds_read_b128 v[224:227], v176 offset:18496
	ds_read_b128 v[220:223], v176 offset:23104
	s_waitcnt lgkmcnt(5)
	v_mfma_f32_32x32x16_bf16 v[32:47], v[228:231], v[244:247], v[32:47]
	s_waitcnt lgkmcnt(4)
	v_mfma_f32_32x32x16_bf16 v[0:15], v[228:231], v[252:255], v[0:15]
	ds_read_b128 v[228:231], v96 offset:59968
	s_waitcnt lgkmcnt(4)
	v_mfma_f32_32x32x16_bf16 v[48:63], v[212:215], v[244:247], v[48:63]
	ds_read_b128 v[244:247], v96 offset:55392
	v_mfma_f32_32x32x16_bf16 v[16:31], v[212:215], v[252:255], v[16:31]
	ds_read_b128 v[212:215], v176 offset:18528
	ds_read_b128 v[252:255], v176 offset:23136
	s_waitcnt lgkmcnt(5)
	v_mfma_f32_32x32x16_bf16 v[32:47], v[216:219], v[224:227], v[32:47]
	s_waitcnt vmcnt(15)
	ds_write_b128 v175, v[64:67]
	global_load_dwordx4 v[64:67], v[152:153], off offset:512
	s_waitcnt lgkmcnt(5)
	v_mfma_f32_32x32x16_bf16 v[0:15], v[216:219], v[220:223], v[0:15]
	ds_read_b128 v[216:219], v96 offset:60000
	s_waitcnt vmcnt(15)
	ds_write_b128 v175, v[68:71] offset:4608
	s_waitcnt vmcnt(14)
	ds_write_b128 v175, v[72:75] offset:9216
	s_waitcnt lgkmcnt(7)
	v_mfma_f32_32x32x16_bf16 v[48:63], v[228:231], v[224:227], v[48:63]
	global_load_dwordx4 v[72:75], v[154:155], off offset:512
	s_waitcnt vmcnt(14)
	ds_write_b128 v175, v[76:79] offset:13824
	v_mfma_f32_32x32x16_bf16 v[16:31], v[228:231], v[220:223], v[16:31]
	global_load_dwordx4 v[76:79], v[156:157], off offset:512
	s_waitcnt vmcnt(14)
	ds_write_b128 v175, v[80:83] offset:36864
	s_waitcnt lgkmcnt(7)
	v_mfma_f32_32x32x16_bf16 v[32:47], v[244:247], v[212:215], v[32:47]
	global_load_dwordx4 v[80:83], v[158:159], off offset:512
	global_load_dwordx4 v[126:129], v[150:151], off offset:512
	s_waitcnt lgkmcnt(6)
	v_mfma_f32_32x32x16_bf16 v[0:15], v[244:247], v[252:255], v[0:15]
	s_waitcnt vmcnt(15)
	ds_write_b128 v175, v[84:87] offset:41472
	global_load_dwordx4 v[134:137], v[160:161], off offset:512
	s_waitcnt lgkmcnt(5)
	v_mfma_f32_32x32x16_bf16 v[48:63], v[216:219], v[212:215], v[48:63]
	s_waitcnt vmcnt(15)
	ds_write_b128 v175, v[88:91] offset:46080
	global_load_dwordx4 v[138:141], v[170:171], off offset:512
	v_mfma_f32_32x32x16_bf16 v[16:31], v[216:219], v[252:255], v[16:31]
	s_waitcnt vmcnt(15)
	ds_write_b128 v175, v[92:95] offset:50688
	global_load_dwordx4 v[142:145], v[172:173], off offset:512
	s_setprio 0
	s_waitcnt lgkmcnt(0)
	s_barrier
	s_setprio 1
	ds_read_b128 v[212:215], v96 offset:36864
	ds_read_b128 v[216:219], v176
	ds_read_b128 v[220:223], v176 offset:4608
	ds_read_b128 v[224:227], v96 offset:41472
	ds_read_b128 v[228:231], v96 offset:36896
	ds_read_b128 v[244:247], v176 offset:32
	ds_read_b128 v[252:255], v176 offset:4640
	s_waitcnt lgkmcnt(5)
	v_mfma_f32_32x32x16_bf16 v[32:47], v[212:215], v[216:219], v[32:47]
	s_waitcnt lgkmcnt(4)
	v_mfma_f32_32x32x16_bf16 v[0:15], v[212:215], v[220:223], v[0:15]
	ds_read_b128 v[212:215], v96 offset:41504
	s_waitcnt lgkmcnt(4)
	v_mfma_f32_32x32x16_bf16 v[48:63], v[224:227], v[216:219], v[48:63]
	ds_read_b128 v[216:219], v96 offset:36928
	v_mfma_f32_32x32x16_bf16 v[16:31], v[224:227], v[220:223], v[16:31]
	ds_read_b128 v[224:227], v176 offset:64
	ds_read_b128 v[220:223], v176 offset:4672
	s_waitcnt lgkmcnt(5)
	v_mfma_f32_32x32x16_bf16 v[32:47], v[228:231], v[244:247], v[32:47]
	s_waitcnt lgkmcnt(4)
	v_mfma_f32_32x32x16_bf16 v[0:15], v[228:231], v[252:255], v[0:15]
	ds_read_b128 v[228:231], v96 offset:41536
	s_waitcnt lgkmcnt(4)
	v_mfma_f32_32x32x16_bf16 v[48:63], v[212:215], v[244:247], v[48:63]
	ds_read_b128 v[244:247], v96 offset:36960
	v_mfma_f32_32x32x16_bf16 v[16:31], v[212:215], v[252:255], v[16:31]
	ds_read_b128 v[212:215], v176 offset:96
	ds_read_b128 v[252:255], v176 offset:4704
	s_waitcnt lgkmcnt(5)
	v_mfma_f32_32x32x16_bf16 v[32:47], v[216:219], v[224:227], v[32:47]
	s_waitcnt vmcnt(15)
	ds_write_b128 v175, v[98:101] offset:18432
	global_load_dwordx4 v[68:71], v[152:153], off offset:640
	s_waitcnt lgkmcnt(5)
	v_mfma_f32_32x32x16_bf16 v[0:15], v[216:219], v[220:223], v[0:15]
	ds_read_b128 v[216:219], v96 offset:41568
	s_waitcnt vmcnt(15)
	ds_write_b128 v175, v[102:105] offset:23040
	global_load_dwordx4 v[84:87], v[154:155], off offset:640
	s_waitcnt lgkmcnt(6)
	v_mfma_f32_32x32x16_bf16 v[48:63], v[228:231], v[224:227], v[48:63]
	s_waitcnt vmcnt(15)
	ds_write_b128 v175, v[106:109] offset:27648
	global_load_dwordx4 v[88:91], v[156:157], off offset:640
	v_mfma_f32_32x32x16_bf16 v[16:31], v[228:231], v[220:223], v[16:31]
	s_waitcnt vmcnt(15)
	ds_write_b128 v175, v[110:113] offset:32256
	global_load_dwordx4 v[92:95], v[158:159], off offset:640
	s_waitcnt lgkmcnt(6)
	v_mfma_f32_32x32x16_bf16 v[32:47], v[244:247], v[212:215], v[32:47]
	s_waitcnt vmcnt(15)
	ds_write_b128 v175, v[114:117] offset:55296
	global_load_dwordx4 v[98:101], v[150:151], off offset:640
	s_waitcnt lgkmcnt(6)
	v_mfma_f32_32x32x16_bf16 v[0:15], v[244:247], v[252:255], v[0:15]
	s_waitcnt vmcnt(15)
	ds_write_b128 v175, v[118:121] offset:59904
	global_load_dwordx4 v[106:109], v[160:161], off offset:640
	s_waitcnt lgkmcnt(5)
	v_mfma_f32_32x32x16_bf16 v[48:63], v[216:219], v[212:215], v[48:63]
	s_waitcnt vmcnt(15)
	ds_write_b128 v175, v[122:125] offset:64512
	global_load_dwordx4 v[110:113], v[170:171], off offset:640
	v_mfma_f32_32x32x16_bf16 v[16:31], v[216:219], v[252:255], v[16:31]
	s_waitcnt vmcnt(15)
	ds_write_b128 v177, v[130:133] offset:13824
	global_load_dwordx4 v[114:117], v[172:173], off offset:640
	s_setprio 0
	s_waitcnt lgkmcnt(0)
	s_barrier
	s_setprio 1
	ds_read_b128 v[212:215], v96 offset:55296
	ds_read_b128 v[216:219], v176 offset:18432
	ds_read_b128 v[220:223], v176 offset:23040
	ds_read_b128 v[224:227], v96 offset:59904
	ds_read_b128 v[228:231], v96 offset:55328
	ds_read_b128 v[244:247], v176 offset:18464
	ds_read_b128 v[252:255], v176 offset:23072
	s_waitcnt lgkmcnt(5)
	v_mfma_f32_32x32x16_bf16 v[32:47], v[212:215], v[216:219], v[32:47]
	s_waitcnt lgkmcnt(4)
	v_mfma_f32_32x32x16_bf16 v[0:15], v[212:215], v[220:223], v[0:15]
	ds_read_b128 v[212:215], v96 offset:59936
	s_waitcnt lgkmcnt(4)
	v_mfma_f32_32x32x16_bf16 v[48:63], v[224:227], v[216:219], v[48:63]
	ds_read_b128 v[216:219], v96 offset:55360
	v_mfma_f32_32x32x16_bf16 v[16:31], v[224:227], v[220:223], v[16:31]
	ds_read_b128 v[224:227], v176 offset:18496
	ds_read_b128 v[220:223], v176 offset:23104
	s_waitcnt lgkmcnt(5)
	v_mfma_f32_32x32x16_bf16 v[32:47], v[228:231], v[244:247], v[32:47]
	s_waitcnt lgkmcnt(4)
	v_mfma_f32_32x32x16_bf16 v[0:15], v[228:231], v[252:255], v[0:15]
	ds_read_b128 v[228:231], v96 offset:59968
	s_waitcnt lgkmcnt(4)
	v_mfma_f32_32x32x16_bf16 v[48:63], v[212:215], v[244:247], v[48:63]
	ds_read_b128 v[244:247], v96 offset:55392
	v_mfma_f32_32x32x16_bf16 v[16:31], v[212:215], v[252:255], v[16:31]
	ds_read_b128 v[212:215], v176 offset:18528
	ds_read_b128 v[252:255], v176 offset:23136
	s_waitcnt lgkmcnt(5)
	v_mfma_f32_32x32x16_bf16 v[32:47], v[216:219], v[224:227], v[32:47]
	s_waitcnt vmcnt(15)
	ds_write_b128 v175, v[64:67]
	global_load_dwordx4 v[64:67], v[152:153], off offset:768
	s_waitcnt lgkmcnt(5)
	v_mfma_f32_32x32x16_bf16 v[0:15], v[216:219], v[220:223], v[0:15]
	ds_read_b128 v[216:219], v96 offset:60000
	s_waitcnt vmcnt(15)
	ds_write_b128 v175, v[72:75] offset:4608
	global_load_dwordx4 v[72:75], v[154:155], off offset:768
	s_waitcnt lgkmcnt(6)
	v_mfma_f32_32x32x16_bf16 v[48:63], v[228:231], v[224:227], v[48:63]
	s_waitcnt vmcnt(15)
	ds_write_b128 v175, v[76:79] offset:9216
	global_load_dwordx4 v[76:79], v[156:157], off offset:768
	v_mfma_f32_32x32x16_bf16 v[16:31], v[228:231], v[220:223], v[16:31]
	s_waitcnt vmcnt(15)
	ds_write_b128 v175, v[80:83] offset:13824
	global_load_dwordx4 v[80:83], v[158:159], off offset:768
	s_waitcnt lgkmcnt(6)
	v_mfma_f32_32x32x16_bf16 v[32:47], v[244:247], v[212:215], v[32:47]
	s_waitcnt vmcnt(15)
	ds_write_b128 v175, v[126:129] offset:36864
	global_load_dwordx4 v[102:105], v[150:151], off offset:768
	s_waitcnt lgkmcnt(6)
	v_mfma_f32_32x32x16_bf16 v[0:15], v[244:247], v[252:255], v[0:15]
	s_waitcnt vmcnt(15)
	ds_write_b128 v175, v[134:137] offset:41472
	global_load_dwordx4 v[118:121], v[160:161], off offset:768
	s_waitcnt lgkmcnt(5)
	v_mfma_f32_32x32x16_bf16 v[48:63], v[216:219], v[212:215], v[48:63]
	s_waitcnt vmcnt(15)
	ds_write_b128 v175, v[138:141] offset:46080
	global_load_dwordx4 v[122:125], v[170:171], off offset:768
	v_mfma_f32_32x32x16_bf16 v[16:31], v[216:219], v[252:255], v[16:31]
	s_waitcnt vmcnt(15)
	ds_write_b128 v175, v[142:145] offset:50688
	global_load_dwordx4 v[126:129], v[172:173], off offset:768
	s_setprio 0
	s_waitcnt lgkmcnt(0)
	s_barrier
	s_setprio 1
	ds_read_b128 v[212:215], v96 offset:36864
	ds_read_b128 v[216:219], v176
	ds_read_b128 v[220:223], v176 offset:4608
	ds_read_b128 v[224:227], v96 offset:41472
	ds_read_b128 v[228:231], v96 offset:36896
	ds_read_b128 v[244:247], v176 offset:32
	ds_read_b128 v[252:255], v176 offset:4640
	s_waitcnt lgkmcnt(5)
	v_mfma_f32_32x32x16_bf16 v[32:47], v[212:215], v[216:219], v[32:47]
	s_waitcnt lgkmcnt(4)
	v_mfma_f32_32x32x16_bf16 v[0:15], v[212:215], v[220:223], v[0:15]
	ds_read_b128 v[212:215], v96 offset:41504
	s_waitcnt lgkmcnt(4)
	v_mfma_f32_32x32x16_bf16 v[48:63], v[224:227], v[216:219], v[48:63]
	ds_read_b128 v[216:219], v96 offset:36928
	v_mfma_f32_32x32x16_bf16 v[16:31], v[224:227], v[220:223], v[16:31]
	ds_read_b128 v[224:227], v176 offset:64
	ds_read_b128 v[220:223], v176 offset:4672
	s_waitcnt lgkmcnt(5)
	v_mfma_f32_32x32x16_bf16 v[32:47], v[228:231], v[244:247], v[32:47]
	s_waitcnt lgkmcnt(4)
	v_mfma_f32_32x32x16_bf16 v[0:15], v[228:231], v[252:255], v[0:15]
	ds_read_b128 v[228:231], v96 offset:41536
	s_waitcnt lgkmcnt(4)
	v_mfma_f32_32x32x16_bf16 v[48:63], v[212:215], v[244:247], v[48:63]
	ds_read_b128 v[244:247], v96 offset:36960
	v_mfma_f32_32x32x16_bf16 v[16:31], v[212:215], v[252:255], v[16:31]
	ds_read_b128 v[212:215], v176 offset:96
	ds_read_b128 v[252:255], v176 offset:4704
	s_waitcnt lgkmcnt(5)
	v_mfma_f32_32x32x16_bf16 v[32:47], v[216:219], v[224:227], v[32:47]
	s_waitcnt vmcnt(15)
	ds_write_b128 v175, v[68:71] offset:18432
	global_load_dwordx4 v[68:71], v[152:153], off offset:896
	s_waitcnt lgkmcnt(5)
	v_mfma_f32_32x32x16_bf16 v[0:15], v[216:219], v[220:223], v[0:15]
	ds_read_b128 v[216:219], v96 offset:41568
	s_waitcnt vmcnt(15)
	ds_write_b128 v175, v[84:87] offset:23040
	global_load_dwordx4 v[84:87], v[154:155], off offset:896
	s_waitcnt lgkmcnt(6)
	v_mfma_f32_32x32x16_bf16 v[48:63], v[228:231], v[224:227], v[48:63]
	s_waitcnt vmcnt(15)
	ds_write_b128 v175, v[88:91] offset:27648
	global_load_dwordx4 v[88:91], v[156:157], off offset:896
	v_mfma_f32_32x32x16_bf16 v[16:31], v[228:231], v[220:223], v[16:31]
	s_waitcnt vmcnt(15)
	ds_write_b128 v175, v[92:95] offset:32256
	global_load_dwordx4 v[92:95], v[158:159], off offset:896
	s_waitcnt lgkmcnt(6)
	v_mfma_f32_32x32x16_bf16 v[32:47], v[244:247], v[212:215], v[32:47]
	s_waitcnt vmcnt(15)
	ds_write_b128 v175, v[98:101] offset:55296
	global_load_dwordx4 v[98:101], v[150:151], off offset:896
	s_waitcnt lgkmcnt(6)
	v_mfma_f32_32x32x16_bf16 v[0:15], v[244:247], v[252:255], v[0:15]
	s_waitcnt vmcnt(15)
	ds_write_b128 v175, v[106:109] offset:59904
	global_load_dwordx4 v[106:109], v[160:161], off offset:896
	s_waitcnt lgkmcnt(5)
	v_mfma_f32_32x32x16_bf16 v[48:63], v[216:219], v[212:215], v[48:63]
	s_waitcnt vmcnt(15)
	ds_write_b128 v175, v[110:113] offset:64512
	global_load_dwordx4 v[110:113], v[170:171], off offset:896
	v_mfma_f32_32x32x16_bf16 v[16:31], v[216:219], v[252:255], v[16:31]
	s_waitcnt vmcnt(15)
	ds_write_b128 v177, v[114:117] offset:13824
	global_load_dwordx4 v[114:117], v[172:173], off offset:896
	s_setprio 0
	s_waitcnt lgkmcnt(0)
	s_barrier
	s_setprio 1
	ds_read_b128 v[212:215], v96 offset:55296
	ds_read_b128 v[216:219], v176 offset:18432
	ds_read_b128 v[220:223], v176 offset:23040
	ds_read_b128 v[224:227], v96 offset:59904
	ds_read_b128 v[228:231], v96 offset:55328
	ds_read_b128 v[244:247], v176 offset:18464
	ds_read_b128 v[252:255], v176 offset:23072
	s_waitcnt lgkmcnt(5)
	v_mfma_f32_32x32x16_bf16 v[32:47], v[212:215], v[216:219], v[32:47]
	s_waitcnt lgkmcnt(4)
	v_mfma_f32_32x32x16_bf16 v[0:15], v[212:215], v[220:223], v[0:15]
	ds_read_b128 v[212:215], v96 offset:59936
	s_waitcnt lgkmcnt(4)
	v_mfma_f32_32x32x16_bf16 v[48:63], v[224:227], v[216:219], v[48:63]
	ds_read_b128 v[216:219], v96 offset:55360
	v_mfma_f32_32x32x16_bf16 v[16:31], v[224:227], v[220:223], v[16:31]
	ds_read_b128 v[224:227], v176 offset:18496
	ds_read_b128 v[220:223], v176 offset:23104
	s_waitcnt lgkmcnt(5)
	v_mfma_f32_32x32x16_bf16 v[32:47], v[228:231], v[244:247], v[32:47]
	s_waitcnt lgkmcnt(4)
	v_mfma_f32_32x32x16_bf16 v[0:15], v[228:231], v[252:255], v[0:15]
	ds_read_b128 v[228:231], v96 offset:59968
	s_waitcnt lgkmcnt(4)
	v_mfma_f32_32x32x16_bf16 v[48:63], v[212:215], v[244:247], v[48:63]
	ds_read_b128 v[244:247], v96 offset:55392
	v_mfma_f32_32x32x16_bf16 v[16:31], v[212:215], v[252:255], v[16:31]
	ds_read_b128 v[212:215], v176 offset:18528
	ds_read_b128 v[252:255], v176 offset:23136
	s_waitcnt lgkmcnt(5)
	v_mfma_f32_32x32x16_bf16 v[32:47], v[216:219], v[224:227], v[32:47]
	s_waitcnt vmcnt(15)
	ds_write_b128 v175, v[64:67]
	global_load_dwordx4 v[64:67], v[152:153], off offset:1024
	s_waitcnt lgkmcnt(5)
	v_mfma_f32_32x32x16_bf16 v[0:15], v[216:219], v[220:223], v[0:15]
	ds_read_b128 v[216:219], v96 offset:60000
	s_waitcnt vmcnt(15)
	ds_write_b128 v175, v[72:75] offset:4608
	global_load_dwordx4 v[72:75], v[154:155], off offset:1024
	s_waitcnt lgkmcnt(6)
	v_mfma_f32_32x32x16_bf16 v[48:63], v[228:231], v[224:227], v[48:63]
	s_waitcnt vmcnt(15)
	ds_write_b128 v175, v[76:79] offset:9216
	global_load_dwordx4 v[76:79], v[156:157], off offset:1024
	v_mfma_f32_32x32x16_bf16 v[16:31], v[228:231], v[220:223], v[16:31]
	s_waitcnt vmcnt(15)
	ds_write_b128 v175, v[80:83] offset:13824
	global_load_dwordx4 v[80:83], v[158:159], off offset:1024
	s_waitcnt lgkmcnt(6)
	v_mfma_f32_32x32x16_bf16 v[32:47], v[244:247], v[212:215], v[32:47]
	s_waitcnt vmcnt(15)
	ds_write_b128 v175, v[102:105] offset:36864
	global_load_dwordx4 v[102:105], v[150:151], off offset:1024
	s_waitcnt lgkmcnt(6)
	v_mfma_f32_32x32x16_bf16 v[0:15], v[244:247], v[252:255], v[0:15]
	s_waitcnt vmcnt(15)
	ds_write_b128 v175, v[118:121] offset:41472
	global_load_dwordx4 v[118:121], v[160:161], off offset:1024
	s_waitcnt lgkmcnt(5)
	v_mfma_f32_32x32x16_bf16 v[48:63], v[216:219], v[212:215], v[48:63]
	s_waitcnt vmcnt(15)
	ds_write_b128 v175, v[122:125] offset:46080
	global_load_dwordx4 v[122:125], v[170:171], off offset:1024
	v_mfma_f32_32x32x16_bf16 v[16:31], v[216:219], v[252:255], v[16:31]
	s_waitcnt vmcnt(15)
	ds_write_b128 v175, v[126:129] offset:50688
	global_load_dwordx4 v[126:129], v[172:173], off offset:1024
	s_setprio 0
	s_waitcnt lgkmcnt(0)
	s_barrier
	s_setprio 1
	ds_read_b128 v[212:215], v96 offset:36864
	ds_read_b128 v[216:219], v176
	ds_read_b128 v[220:223], v176 offset:4608
	ds_read_b128 v[224:227], v96 offset:41472
	ds_read_b128 v[228:231], v96 offset:36896
	ds_read_b128 v[244:247], v176 offset:32
	ds_read_b128 v[252:255], v176 offset:4640
	s_waitcnt lgkmcnt(5)
	v_mfma_f32_32x32x16_bf16 v[32:47], v[212:215], v[216:219], v[32:47]
	s_waitcnt lgkmcnt(4)
	v_mfma_f32_32x32x16_bf16 v[0:15], v[212:215], v[220:223], v[0:15]
	ds_read_b128 v[212:215], v96 offset:41504
	s_waitcnt lgkmcnt(4)
	v_mfma_f32_32x32x16_bf16 v[48:63], v[224:227], v[216:219], v[48:63]
	ds_read_b128 v[216:219], v96 offset:36928
	v_mfma_f32_32x32x16_bf16 v[16:31], v[224:227], v[220:223], v[16:31]
	ds_read_b128 v[224:227], v176 offset:64
	ds_read_b128 v[220:223], v176 offset:4672
	s_waitcnt lgkmcnt(5)
	v_mfma_f32_32x32x16_bf16 v[32:47], v[228:231], v[244:247], v[32:47]
	s_waitcnt lgkmcnt(4)
	v_mfma_f32_32x32x16_bf16 v[0:15], v[228:231], v[252:255], v[0:15]
	ds_read_b128 v[228:231], v96 offset:41536
	s_waitcnt lgkmcnt(4)
	v_mfma_f32_32x32x16_bf16 v[48:63], v[212:215], v[244:247], v[48:63]
	ds_read_b128 v[244:247], v96 offset:36960
	v_mfma_f32_32x32x16_bf16 v[16:31], v[212:215], v[252:255], v[16:31]
	ds_read_b128 v[212:215], v176 offset:96
	ds_read_b128 v[252:255], v176 offset:4704
	s_waitcnt lgkmcnt(5)
	v_mfma_f32_32x32x16_bf16 v[32:47], v[216:219], v[224:227], v[32:47]
	s_waitcnt vmcnt(15)
	ds_write_b128 v175, v[68:71] offset:18432
	global_load_dwordx4 v[68:71], v[152:153], off offset:1152
	s_waitcnt lgkmcnt(5)
	v_mfma_f32_32x32x16_bf16 v[0:15], v[216:219], v[220:223], v[0:15]
	ds_read_b128 v[216:219], v96 offset:41568
	s_waitcnt vmcnt(15)
	ds_write_b128 v175, v[84:87] offset:23040
	global_load_dwordx4 v[84:87], v[154:155], off offset:1152
	s_waitcnt lgkmcnt(6)
	v_mfma_f32_32x32x16_bf16 v[48:63], v[228:231], v[224:227], v[48:63]
	s_waitcnt vmcnt(15)
	ds_write_b128 v175, v[88:91] offset:27648
	global_load_dwordx4 v[88:91], v[156:157], off offset:1152
	v_mfma_f32_32x32x16_bf16 v[16:31], v[228:231], v[220:223], v[16:31]
	s_waitcnt vmcnt(15)
	ds_write_b128 v175, v[92:95] offset:32256
	global_load_dwordx4 v[92:95], v[158:159], off offset:1152
	s_waitcnt lgkmcnt(6)
	v_mfma_f32_32x32x16_bf16 v[32:47], v[244:247], v[212:215], v[32:47]
	s_waitcnt vmcnt(15)
	ds_write_b128 v175, v[98:101] offset:55296
	global_load_dwordx4 v[98:101], v[150:151], off offset:1152
	s_waitcnt lgkmcnt(6)
	v_mfma_f32_32x32x16_bf16 v[0:15], v[244:247], v[252:255], v[0:15]
	s_waitcnt vmcnt(15)
	ds_write_b128 v175, v[106:109] offset:59904
	global_load_dwordx4 v[106:109], v[160:161], off offset:1152
	s_waitcnt lgkmcnt(5)
	v_mfma_f32_32x32x16_bf16 v[48:63], v[216:219], v[212:215], v[48:63]
	s_waitcnt vmcnt(15)
	ds_write_b128 v175, v[110:113] offset:64512
	global_load_dwordx4 v[110:113], v[170:171], off offset:1152
	v_mfma_f32_32x32x16_bf16 v[16:31], v[216:219], v[252:255], v[16:31]
	s_waitcnt vmcnt(15)
	ds_write_b128 v177, v[114:117] offset:13824
	global_load_dwordx4 v[114:117], v[172:173], off offset:1152
	s_setprio 0
	s_waitcnt lgkmcnt(0)
	s_barrier
	s_setprio 1
	ds_read_b128 v[212:215], v96 offset:55296
	ds_read_b128 v[216:219], v176 offset:18432
	ds_read_b128 v[220:223], v176 offset:23040
	ds_read_b128 v[224:227], v96 offset:59904
	ds_read_b128 v[228:231], v96 offset:55328
	ds_read_b128 v[244:247], v176 offset:18464
	ds_read_b128 v[252:255], v176 offset:23072
	s_waitcnt lgkmcnt(5)
	v_mfma_f32_32x32x16_bf16 v[32:47], v[212:215], v[216:219], v[32:47]
	s_waitcnt lgkmcnt(4)
	v_mfma_f32_32x32x16_bf16 v[0:15], v[212:215], v[220:223], v[0:15]
	ds_read_b128 v[212:215], v96 offset:59936
	s_waitcnt lgkmcnt(4)
	v_mfma_f32_32x32x16_bf16 v[48:63], v[224:227], v[216:219], v[48:63]
	ds_read_b128 v[216:219], v96 offset:55360
	v_mfma_f32_32x32x16_bf16 v[16:31], v[224:227], v[220:223], v[16:31]
	ds_read_b128 v[224:227], v176 offset:18496
	ds_read_b128 v[220:223], v176 offset:23104
	s_waitcnt lgkmcnt(5)
	v_mfma_f32_32x32x16_bf16 v[32:47], v[228:231], v[244:247], v[32:47]
	s_waitcnt lgkmcnt(4)
	v_mfma_f32_32x32x16_bf16 v[0:15], v[228:231], v[252:255], v[0:15]
	ds_read_b128 v[228:231], v96 offset:59968
	s_waitcnt lgkmcnt(4)
	v_mfma_f32_32x32x16_bf16 v[48:63], v[212:215], v[244:247], v[48:63]
	ds_read_b128 v[244:247], v96 offset:55392
	v_mfma_f32_32x32x16_bf16 v[16:31], v[212:215], v[252:255], v[16:31]
	ds_read_b128 v[212:215], v176 offset:18528
	ds_read_b128 v[252:255], v176 offset:23136
	s_waitcnt lgkmcnt(5)
	v_mfma_f32_32x32x16_bf16 v[32:47], v[216:219], v[224:227], v[32:47]
	s_waitcnt vmcnt(15)
	ds_write_b128 v175, v[64:67]
	global_load_dwordx4 v[64:67], v[152:153], off offset:1280
	s_waitcnt lgkmcnt(5)
	v_mfma_f32_32x32x16_bf16 v[0:15], v[216:219], v[220:223], v[0:15]
	ds_read_b128 v[216:219], v96 offset:60000
	s_waitcnt vmcnt(15)
	ds_write_b128 v175, v[72:75] offset:4608
	global_load_dwordx4 v[72:75], v[154:155], off offset:1280
	s_waitcnt lgkmcnt(6)
	v_mfma_f32_32x32x16_bf16 v[48:63], v[228:231], v[224:227], v[48:63]
	s_waitcnt vmcnt(15)
	ds_write_b128 v175, v[76:79] offset:9216
	global_load_dwordx4 v[76:79], v[156:157], off offset:1280
	v_mfma_f32_32x32x16_bf16 v[16:31], v[228:231], v[220:223], v[16:31]
	s_waitcnt vmcnt(15)
	ds_write_b128 v175, v[80:83] offset:13824
	global_load_dwordx4 v[80:83], v[158:159], off offset:1280
	s_waitcnt lgkmcnt(6)
	v_mfma_f32_32x32x16_bf16 v[32:47], v[244:247], v[212:215], v[32:47]
	s_waitcnt vmcnt(15)
	ds_write_b128 v175, v[102:105] offset:36864
	global_load_dwordx4 v[102:105], v[150:151], off offset:1280
	s_waitcnt lgkmcnt(6)
	v_mfma_f32_32x32x16_bf16 v[0:15], v[244:247], v[252:255], v[0:15]
	s_waitcnt vmcnt(15)
	ds_write_b128 v175, v[118:121] offset:41472
	global_load_dwordx4 v[118:121], v[160:161], off offset:1280
	s_waitcnt lgkmcnt(5)
	v_mfma_f32_32x32x16_bf16 v[48:63], v[216:219], v[212:215], v[48:63]
	s_waitcnt vmcnt(15)
	ds_write_b128 v175, v[122:125] offset:46080
	global_load_dwordx4 v[122:125], v[170:171], off offset:1280
	v_mfma_f32_32x32x16_bf16 v[16:31], v[216:219], v[252:255], v[16:31]
	s_waitcnt vmcnt(15)
	ds_write_b128 v175, v[126:129] offset:50688
	global_load_dwordx4 v[126:129], v[172:173], off offset:1280
	s_setprio 0
	s_waitcnt lgkmcnt(0)
	s_barrier
	s_setprio 1
	ds_read_b128 v[212:215], v96 offset:36864
	ds_read_b128 v[216:219], v176
	ds_read_b128 v[220:223], v176 offset:4608
	ds_read_b128 v[224:227], v96 offset:41472
	ds_read_b128 v[228:231], v96 offset:36896
	ds_read_b128 v[244:247], v176 offset:32
	ds_read_b128 v[252:255], v176 offset:4640
	s_waitcnt lgkmcnt(5)
	v_mfma_f32_32x32x16_bf16 v[32:47], v[212:215], v[216:219], v[32:47]
	s_waitcnt lgkmcnt(4)
	v_mfma_f32_32x32x16_bf16 v[0:15], v[212:215], v[220:223], v[0:15]
	ds_read_b128 v[212:215], v96 offset:41504
	s_waitcnt lgkmcnt(4)
	v_mfma_f32_32x32x16_bf16 v[48:63], v[224:227], v[216:219], v[48:63]
	ds_read_b128 v[216:219], v96 offset:36928
	v_mfma_f32_32x32x16_bf16 v[16:31], v[224:227], v[220:223], v[16:31]
	ds_read_b128 v[224:227], v176 offset:64
	ds_read_b128 v[220:223], v176 offset:4672
	s_waitcnt lgkmcnt(5)
	v_mfma_f32_32x32x16_bf16 v[32:47], v[228:231], v[244:247], v[32:47]
	s_waitcnt lgkmcnt(4)
	v_mfma_f32_32x32x16_bf16 v[0:15], v[228:231], v[252:255], v[0:15]
	ds_read_b128 v[228:231], v96 offset:41536
	s_waitcnt lgkmcnt(4)
	v_mfma_f32_32x32x16_bf16 v[48:63], v[212:215], v[244:247], v[48:63]
	ds_read_b128 v[244:247], v96 offset:36960
	v_mfma_f32_32x32x16_bf16 v[16:31], v[212:215], v[252:255], v[16:31]
	ds_read_b128 v[212:215], v176 offset:96
	ds_read_b128 v[252:255], v176 offset:4704
	s_waitcnt lgkmcnt(5)
	v_mfma_f32_32x32x16_bf16 v[32:47], v[216:219], v[224:227], v[32:47]
	s_waitcnt vmcnt(15)
	ds_write_b128 v175, v[68:71] offset:18432
	global_load_dwordx4 v[68:71], v[152:153], off offset:1408
	s_waitcnt lgkmcnt(5)
	v_mfma_f32_32x32x16_bf16 v[0:15], v[216:219], v[220:223], v[0:15]
	ds_read_b128 v[216:219], v96 offset:41568
	s_waitcnt vmcnt(15)
	ds_write_b128 v175, v[84:87] offset:23040
	global_load_dwordx4 v[84:87], v[154:155], off offset:1408
	s_waitcnt lgkmcnt(6)
	v_mfma_f32_32x32x16_bf16 v[48:63], v[228:231], v[224:227], v[48:63]
	s_waitcnt vmcnt(15)
	ds_write_b128 v175, v[88:91] offset:27648
	global_load_dwordx4 v[88:91], v[156:157], off offset:1408
	v_mfma_f32_32x32x16_bf16 v[16:31], v[228:231], v[220:223], v[16:31]
	s_waitcnt vmcnt(15)
	ds_write_b128 v175, v[92:95] offset:32256
	global_load_dwordx4 v[92:95], v[158:159], off offset:1408
	s_waitcnt lgkmcnt(6)
	v_mfma_f32_32x32x16_bf16 v[32:47], v[244:247], v[212:215], v[32:47]
	s_waitcnt vmcnt(15)
	ds_write_b128 v175, v[98:101] offset:55296
	global_load_dwordx4 v[98:101], v[150:151], off offset:1408
	s_waitcnt lgkmcnt(6)
	v_mfma_f32_32x32x16_bf16 v[0:15], v[244:247], v[252:255], v[0:15]
	s_waitcnt vmcnt(15)
	ds_write_b128 v175, v[106:109] offset:59904
	global_load_dwordx4 v[106:109], v[160:161], off offset:1408
	s_waitcnt lgkmcnt(5)
	v_mfma_f32_32x32x16_bf16 v[48:63], v[216:219], v[212:215], v[48:63]
	s_waitcnt vmcnt(15)
	ds_write_b128 v175, v[110:113] offset:64512
	global_load_dwordx4 v[110:113], v[170:171], off offset:1408
	v_mfma_f32_32x32x16_bf16 v[16:31], v[216:219], v[252:255], v[16:31]
	s_waitcnt vmcnt(15)
	ds_write_b128 v177, v[114:117] offset:13824
	global_load_dwordx4 v[130:133], v[172:173], off offset:1408
	s_setprio 0
	s_waitcnt lgkmcnt(0)
	s_barrier
	s_setprio 1
	ds_read_b128 v[212:215], v96 offset:55296
	ds_read_b128 v[216:219], v176 offset:18432
	ds_read_b128 v[220:223], v176 offset:23040
	ds_read_b128 v[224:227], v96 offset:59904
	ds_read_b128 v[228:231], v96 offset:55328
	ds_read_b128 v[244:247], v176 offset:18464
	ds_read_b128 v[252:255], v176 offset:23072
	s_waitcnt lgkmcnt(5)
	v_mfma_f32_32x32x16_bf16 v[32:47], v[212:215], v[216:219], v[32:47]
	s_waitcnt lgkmcnt(4)
	v_mfma_f32_32x32x16_bf16 v[0:15], v[212:215], v[220:223], v[0:15]
	ds_read_b128 v[212:215], v96 offset:59936
	s_waitcnt lgkmcnt(4)
	v_mfma_f32_32x32x16_bf16 v[48:63], v[224:227], v[216:219], v[48:63]
	ds_read_b128 v[216:219], v96 offset:55360
	v_mfma_f32_32x32x16_bf16 v[16:31], v[224:227], v[220:223], v[16:31]
	ds_read_b128 v[224:227], v176 offset:18496
	ds_read_b128 v[220:223], v176 offset:23104
	s_waitcnt lgkmcnt(5)
	v_mfma_f32_32x32x16_bf16 v[32:47], v[228:231], v[244:247], v[32:47]
	s_waitcnt lgkmcnt(4)
	v_mfma_f32_32x32x16_bf16 v[0:15], v[228:231], v[252:255], v[0:15]
	ds_read_b128 v[228:231], v96 offset:59968
	s_waitcnt lgkmcnt(4)
	v_mfma_f32_32x32x16_bf16 v[48:63], v[212:215], v[244:247], v[48:63]
	ds_read_b128 v[244:247], v96 offset:55392
	v_mfma_f32_32x32x16_bf16 v[16:31], v[212:215], v[252:255], v[16:31]
	ds_read_b128 v[212:215], v176 offset:18528
	ds_read_b128 v[252:255], v176 offset:23136
	s_waitcnt lgkmcnt(5)
	v_mfma_f32_32x32x16_bf16 v[32:47], v[216:219], v[224:227], v[32:47]
	s_waitcnt vmcnt(15)
	ds_write_b128 v175, v[64:67]
	global_load_dwordx4 v[64:67], v[152:153], off offset:1536
	s_waitcnt lgkmcnt(5)
	v_mfma_f32_32x32x16_bf16 v[0:15], v[216:219], v[220:223], v[0:15]
	ds_read_b128 v[216:219], v96 offset:60000
	s_waitcnt vmcnt(15)
	ds_write_b128 v175, v[72:75] offset:4608
	global_load_dwordx4 v[72:75], v[154:155], off offset:1536
	s_waitcnt lgkmcnt(6)
	v_mfma_f32_32x32x16_bf16 v[48:63], v[228:231], v[224:227], v[48:63]
	s_waitcnt vmcnt(15)
	ds_write_b128 v175, v[76:79] offset:9216
	global_load_dwordx4 v[76:79], v[156:157], off offset:1536
	v_mfma_f32_32x32x16_bf16 v[16:31], v[228:231], v[220:223], v[16:31]
	s_waitcnt vmcnt(15)
	ds_write_b128 v175, v[80:83] offset:13824
	global_load_dwordx4 v[80:83], v[158:159], off offset:1536
	s_waitcnt lgkmcnt(6)
	v_mfma_f32_32x32x16_bf16 v[32:47], v[244:247], v[212:215], v[32:47]
	s_waitcnt vmcnt(15)
	ds_write_b128 v175, v[102:105] offset:36864
	global_load_dwordx4 v[114:117], v[150:151], off offset:1536
	s_waitcnt lgkmcnt(6)
	v_mfma_f32_32x32x16_bf16 v[0:15], v[244:247], v[252:255], v[0:15]
	s_waitcnt vmcnt(15)
	ds_write_b128 v175, v[118:121] offset:41472
	s_waitcnt vmcnt(14)
	ds_write_b128 v175, v[122:125] offset:46080
	s_waitcnt lgkmcnt(6)
	v_mfma_f32_32x32x16_bf16 v[48:63], v[216:219], v[212:215], v[48:63]
	global_load_dwordx4 v[122:125], v[160:161], off offset:1536
	s_waitcnt vmcnt(14)
	ds_write_b128 v175, v[126:129] offset:50688
	v_mfma_f32_32x32x16_bf16 v[16:31], v[216:219], v[252:255], v[16:31]
	global_load_dwordx4 v[126:129], v[170:171], off offset:1536
	global_load_dwordx4 v[134:137], v[172:173], off offset:1536
	s_setprio 0
	s_waitcnt lgkmcnt(0)
	s_barrier
	s_setprio 1
	ds_read_b128 v[212:215], v96 offset:36864
	ds_read_b128 v[216:219], v176
	ds_read_b128 v[220:223], v176 offset:4608
	ds_read_b128 v[224:227], v96 offset:41472
	ds_read_b128 v[228:231], v96 offset:36896
	ds_read_b128 v[244:247], v176 offset:32
	ds_read_b128 v[252:255], v176 offset:4640
	s_waitcnt lgkmcnt(5)
	v_mfma_f32_32x32x16_bf16 v[32:47], v[212:215], v[216:219], v[32:47]
	s_waitcnt lgkmcnt(4)
	v_mfma_f32_32x32x16_bf16 v[0:15], v[212:215], v[220:223], v[0:15]
	ds_read_b128 v[212:215], v96 offset:41504
	s_waitcnt lgkmcnt(4)
	v_mfma_f32_32x32x16_bf16 v[48:63], v[224:227], v[216:219], v[48:63]
	ds_read_b128 v[216:219], v96 offset:36928
	v_mfma_f32_32x32x16_bf16 v[16:31], v[224:227], v[220:223], v[16:31]
	ds_read_b128 v[224:227], v176 offset:64
	ds_read_b128 v[220:223], v176 offset:4672
	s_waitcnt lgkmcnt(5)
	v_mfma_f32_32x32x16_bf16 v[32:47], v[228:231], v[244:247], v[32:47]
	s_waitcnt lgkmcnt(4)
	v_mfma_f32_32x32x16_bf16 v[0:15], v[228:231], v[252:255], v[0:15]
	ds_read_b128 v[228:231], v96 offset:41536
	s_waitcnt lgkmcnt(4)
	v_mfma_f32_32x32x16_bf16 v[48:63], v[212:215], v[244:247], v[48:63]
	ds_read_b128 v[244:247], v96 offset:36960
	v_mfma_f32_32x32x16_bf16 v[16:31], v[212:215], v[252:255], v[16:31]
	ds_read_b128 v[212:215], v176 offset:96
	ds_read_b128 v[252:255], v176 offset:4704
	s_waitcnt lgkmcnt(5)
	v_mfma_f32_32x32x16_bf16 v[32:47], v[216:219], v[224:227], v[32:47]
	s_waitcnt vmcnt(15)
	ds_write_b128 v175, v[68:71] offset:18432
	s_waitcnt vmcnt(14)
	ds_write_b128 v175, v[84:87] offset:23040
	s_waitcnt lgkmcnt(6)
	v_mfma_f32_32x32x16_bf16 v[0:15], v[216:219], v[220:223], v[0:15]
	ds_read_b128 v[216:219], v96 offset:41568
	s_waitcnt vmcnt(13)
	ds_write_b128 v175, v[88:91] offset:27648
	s_waitcnt vmcnt(12)
	ds_write_b128 v175, v[92:95] offset:32256
	s_waitcnt lgkmcnt(8)
	v_mfma_f32_32x32x16_bf16 v[48:63], v[228:231], v[224:227], v[48:63]
	s_waitcnt vmcnt(11)
	ds_write_b128 v175, v[98:101] offset:55296
	v_mfma_f32_32x32x16_bf16 v[16:31], v[228:231], v[220:223], v[16:31]
	global_load_dwordx4 v[98:101], v[152:153], off offset:1664
	global_load_dwordx4 v[102:105], v[154:155], off offset:1664
	s_waitcnt vmcnt(12)
	ds_write_b128 v175, v[106:109] offset:59904
	s_waitcnt lgkmcnt(8)
	v_mfma_f32_32x32x16_bf16 v[32:47], v[244:247], v[212:215], v[32:47]
	global_load_dwordx4 v[106:109], v[156:157], off offset:1664
	s_waitcnt vmcnt(12)
	ds_write_b128 v175, v[110:113] offset:64512
	s_waitcnt lgkmcnt(8)
	v_mfma_f32_32x32x16_bf16 v[0:15], v[244:247], v[252:255], v[0:15]
	global_load_dwordx4 v[110:113], v[158:159], off offset:1664
	global_load_dwordx4 v[118:121], v[150:151], off offset:1664
	s_waitcnt lgkmcnt(5)
	v_mfma_f32_32x32x16_bf16 v[48:63], v[216:219], v[212:215], v[48:63]
	s_waitcnt vmcnt(13)
	ds_write_b128 v177, v[130:133] offset:13824
	global_load_dwordx4 v[130:133], v[160:161], off offset:1664
	v_mfma_f32_32x32x16_bf16 v[16:31], v[216:219], v[252:255], v[16:31]
	global_load_dwordx4 v[138:141], v[170:171], off offset:1664
	global_load_dwordx4 v[142:145], v[172:173], off offset:1664
	s_setprio 0
	s_waitcnt lgkmcnt(0)
	s_barrier
	s_setprio 1
	ds_read_b128 v[212:215], v96 offset:55296
	ds_read_b128 v[216:219], v176 offset:18432
	ds_read_b128 v[220:223], v176 offset:23040
	ds_read_b128 v[224:227], v96 offset:59904
	ds_read_b128 v[228:231], v96 offset:55328
	ds_read_b128 v[244:247], v176 offset:18464
	ds_read_b128 v[252:255], v176 offset:23072
	s_waitcnt lgkmcnt(5)
	v_mfma_f32_32x32x16_bf16 v[32:47], v[212:215], v[216:219], v[32:47]
	s_waitcnt lgkmcnt(4)
	v_mfma_f32_32x32x16_bf16 v[0:15], v[212:215], v[220:223], v[0:15]
	ds_read_b128 v[212:215], v96 offset:59936
	s_waitcnt lgkmcnt(4)
	v_mfma_f32_32x32x16_bf16 v[48:63], v[224:227], v[216:219], v[48:63]
	ds_read_b128 v[216:219], v96 offset:55360
	v_mfma_f32_32x32x16_bf16 v[16:31], v[224:227], v[220:223], v[16:31]
	ds_read_b128 v[224:227], v176 offset:18496
	ds_read_b128 v[220:223], v176 offset:23104
	s_waitcnt lgkmcnt(5)
	v_mfma_f32_32x32x16_bf16 v[32:47], v[228:231], v[244:247], v[32:47]
	s_waitcnt lgkmcnt(4)
	v_mfma_f32_32x32x16_bf16 v[0:15], v[228:231], v[252:255], v[0:15]
	ds_read_b128 v[228:231], v96 offset:59968
	s_waitcnt lgkmcnt(4)
	v_mfma_f32_32x32x16_bf16 v[48:63], v[212:215], v[244:247], v[48:63]
	ds_read_b128 v[244:247], v96 offset:55392
	v_mfma_f32_32x32x16_bf16 v[16:31], v[212:215], v[252:255], v[16:31]
	ds_read_b128 v[212:215], v176 offset:18528
	ds_read_b128 v[252:255], v176 offset:23136
	s_waitcnt lgkmcnt(5)
	v_mfma_f32_32x32x16_bf16 v[32:47], v[216:219], v[224:227], v[32:47]
	s_waitcnt vmcnt(15)
	ds_write_b128 v175, v[64:67]
	global_load_dwordx4 v[64:67], v[152:153], off offset:1792
	s_waitcnt lgkmcnt(5)
	v_mfma_f32_32x32x16_bf16 v[0:15], v[216:219], v[220:223], v[0:15]
	ds_read_b128 v[216:219], v96 offset:60000
	s_waitcnt vmcnt(15)
	ds_write_b128 v175, v[72:75] offset:4608
	global_load_dwordx4 v[68:71], v[154:155], off offset:1792
	s_waitcnt lgkmcnt(6)
	v_mfma_f32_32x32x16_bf16 v[48:63], v[228:231], v[224:227], v[48:63]
	s_waitcnt vmcnt(15)
	ds_write_b128 v175, v[76:79] offset:9216
	global_load_dwordx4 v[72:75], v[156:157], off offset:1792
	v_mfma_f32_32x32x16_bf16 v[16:31], v[228:231], v[220:223], v[16:31]
	s_waitcnt vmcnt(15)
	ds_write_b128 v175, v[80:83] offset:13824
	global_load_dwordx4 v[76:79], v[158:159], off offset:1792
	s_waitcnt lgkmcnt(6)
	v_mfma_f32_32x32x16_bf16 v[32:47], v[244:247], v[212:215], v[32:47]
	s_waitcnt vmcnt(15)
	ds_write_b128 v175, v[114:117] offset:36864
	global_load_dwordx4 v[80:83], v[150:151], off offset:1792
	s_waitcnt lgkmcnt(6)
	v_mfma_f32_32x32x16_bf16 v[0:15], v[244:247], v[252:255], v[0:15]
	s_waitcnt vmcnt(15)
	ds_write_b128 v175, v[122:125] offset:41472
	global_load_dwordx4 v[84:87], v[160:161], off offset:1792
	s_waitcnt lgkmcnt(5)
	v_mfma_f32_32x32x16_bf16 v[48:63], v[216:219], v[212:215], v[48:63]
	s_waitcnt vmcnt(15)
	ds_write_b128 v175, v[126:129] offset:46080
	global_load_dwordx4 v[88:91], v[170:171], off offset:1792
	v_mfma_f32_32x32x16_bf16 v[16:31], v[216:219], v[252:255], v[16:31]
	s_waitcnt vmcnt(15)
	ds_write_b128 v175, v[134:137] offset:50688
	global_load_dwordx4 v[92:95], v[172:173], off offset:1792
	s_setprio 0
	s_waitcnt lgkmcnt(0)
	s_barrier
	s_setprio 1
	ds_read_b128 v[212:215], v96 offset:36864
	ds_read_b128 v[216:219], v176
	ds_read_b128 v[220:223], v176 offset:4608
	ds_read_b128 v[224:227], v96 offset:41472
	ds_read_b128 v[228:231], v96 offset:36896
	ds_read_b128 v[244:247], v176 offset:32
	ds_read_b128 v[252:255], v176 offset:4640
	s_waitcnt lgkmcnt(5)
	v_mfma_f32_32x32x16_bf16 v[32:47], v[212:215], v[216:219], v[32:47]
	s_waitcnt lgkmcnt(4)
	v_mfma_f32_32x32x16_bf16 v[0:15], v[212:215], v[220:223], v[0:15]
	ds_read_b128 v[212:215], v96 offset:41504
	s_waitcnt lgkmcnt(4)
	v_mfma_f32_32x32x16_bf16 v[48:63], v[224:227], v[216:219], v[48:63]
	ds_read_b128 v[216:219], v96 offset:36928
	v_mfma_f32_32x32x16_bf16 v[16:31], v[224:227], v[220:223], v[16:31]
	ds_read_b128 v[224:227], v176 offset:64
	ds_read_b128 v[220:223], v176 offset:4672
	s_waitcnt lgkmcnt(5)
	v_mfma_f32_32x32x16_bf16 v[32:47], v[228:231], v[244:247], v[32:47]
	s_waitcnt lgkmcnt(4)
	v_mfma_f32_32x32x16_bf16 v[0:15], v[228:231], v[252:255], v[0:15]
	ds_read_b128 v[228:231], v96 offset:41536
	s_waitcnt lgkmcnt(4)
	v_mfma_f32_32x32x16_bf16 v[48:63], v[212:215], v[244:247], v[48:63]
	ds_read_b128 v[244:247], v96 offset:36960
	v_mfma_f32_32x32x16_bf16 v[16:31], v[212:215], v[252:255], v[16:31]
	ds_read_b128 v[212:215], v176 offset:96
	ds_read_b128 v[252:255], v176 offset:4704
	s_waitcnt lgkmcnt(5)
	v_mfma_f32_32x32x16_bf16 v[32:47], v[216:219], v[224:227], v[32:47]
	s_waitcnt vmcnt(15)
	ds_write_b128 v175, v[98:101] offset:18432
	s_waitcnt vmcnt(14)
	ds_write_b128 v175, v[102:105] offset:23040
	s_waitcnt lgkmcnt(6)
	v_mfma_f32_32x32x16_bf16 v[0:15], v[216:219], v[220:223], v[0:15]
	ds_read_b128 v[216:219], v96 offset:41568
	global_load_dwordx4 v[100:103], v[152:153], off offset:1920
	s_waitcnt vmcnt(14)
	ds_write_b128 v175, v[106:109] offset:27648
	s_waitcnt lgkmcnt(7)
	v_mfma_f32_32x32x16_bf16 v[48:63], v[228:231], v[224:227], v[48:63]
	global_load_dwordx4 v[104:107], v[154:155], off offset:1920
	s_waitcnt vmcnt(14)
	ds_write_b128 v175, v[110:113] offset:32256
	v_mfma_f32_32x32x16_bf16 v[16:31], v[228:231], v[220:223], v[16:31]
	global_load_dwordx4 v[108:111], v[156:157], off offset:1920
	global_load_dwordx4 v[112:115], v[158:159], off offset:1920
	s_waitcnt lgkmcnt(6)
	v_mfma_f32_32x32x16_bf16 v[32:47], v[244:247], v[212:215], v[32:47]
	s_waitcnt vmcnt(15)
	ds_write_b128 v175, v[118:121] offset:55296
	global_load_dwordx4 v[116:119], v[150:151], off offset:1920
	s_waitcnt lgkmcnt(6)
	v_mfma_f32_32x32x16_bf16 v[0:15], v[244:247], v[252:255], v[0:15]
	s_waitcnt vmcnt(15)
	ds_write_b128 v175, v[130:133] offset:59904
	global_load_dwordx4 v[124:127], v[160:161], off offset:1920
	s_waitcnt lgkmcnt(4)
	v_mfma_f32_32x32x16_bf16 v[48:63], v[216:219], v[212:215], v[48:63]
	s_waitcnt vmcnt(15)
	ds_write_b128 v175, v[138:141] offset:64512
	global_load_dwordx4 v[120:123], v[170:171], off offset:1920
	v_mfma_f32_32x32x16_bf16 v[16:31], v[216:219], v[252:255], v[16:31]
	s_waitcnt vmcnt(15)
	ds_write_b128 v177, v[142:145] offset:13824
	global_load_dwordx4 v[128:131], v[172:173], off offset:1920
	s_setprio 0
	s_waitcnt lgkmcnt(0)
	s_barrier
	s_setprio 1
	ds_read_b128 v[212:215], v96 offset:55296
	ds_read_b128 v[216:219], v176 offset:18432
	ds_read_b128 v[220:223], v176 offset:23040
	ds_read_b128 v[224:227], v96 offset:59904
	ds_read_b128 v[228:231], v96 offset:55328
	ds_read_b128 v[244:247], v176 offset:18464
	ds_read_b128 v[252:255], v176 offset:23072
	s_waitcnt lgkmcnt(5)
	v_mfma_f32_32x32x16_bf16 v[32:47], v[212:215], v[216:219], v[32:47]
	s_waitcnt lgkmcnt(4)
	v_mfma_f32_32x32x16_bf16 v[0:15], v[212:215], v[220:223], v[0:15]
	ds_read_b128 v[212:215], v96 offset:59936
	s_waitcnt lgkmcnt(4)
	v_mfma_f32_32x32x16_bf16 v[48:63], v[224:227], v[216:219], v[48:63]
	ds_read_b128 v[216:219], v96 offset:55360
	v_mfma_f32_32x32x16_bf16 v[16:31], v[224:227], v[220:223], v[16:31]
	ds_read_b128 v[224:227], v176 offset:18496
	ds_read_b128 v[220:223], v176 offset:23104
	s_waitcnt lgkmcnt(5)
	v_mfma_f32_32x32x16_bf16 v[32:47], v[228:231], v[244:247], v[32:47]
	s_waitcnt lgkmcnt(4)
	v_mfma_f32_32x32x16_bf16 v[0:15], v[228:231], v[252:255], v[0:15]
	ds_read_b128 v[228:231], v96 offset:59968
	s_waitcnt lgkmcnt(4)
	v_mfma_f32_32x32x16_bf16 v[48:63], v[212:215], v[244:247], v[48:63]
	ds_read_b128 v[244:247], v96 offset:55392
	v_mfma_f32_32x32x16_bf16 v[16:31], v[212:215], v[252:255], v[16:31]
	ds_read_b128 v[212:215], v176 offset:18528
	ds_read_b128 v[252:255], v176 offset:23136
	s_waitcnt lgkmcnt(5)
	v_mfma_f32_32x32x16_bf16 v[32:47], v[216:219], v[224:227], v[32:47]
	s_waitcnt lgkmcnt(4)
	v_mfma_f32_32x32x16_bf16 v[0:15], v[216:219], v[220:223], v[0:15]
	ds_read_b128 v[216:219], v96 offset:60000
	s_waitcnt lgkmcnt(4)
	v_mfma_f32_32x32x16_bf16 v[48:63], v[228:231], v[224:227], v[48:63]
	v_mfma_f32_32x32x16_bf16 v[16:31], v[228:231], v[220:223], v[16:31]
	s_waitcnt lgkmcnt(2)
	v_mfma_f32_32x32x16_bf16 v[32:47], v[244:247], v[212:215], v[32:47]
	s_waitcnt lgkmcnt(1)
	v_mfma_f32_32x32x16_bf16 v[0:15], v[244:247], v[252:255], v[0:15]
	s_waitcnt lgkmcnt(0)
	v_mfma_f32_32x32x16_bf16 v[48:63], v[216:219], v[212:215], v[48:63]
	v_mfma_f32_32x32x16_bf16 v[16:31], v[216:219], v[252:255], v[16:31]
	s_setprio 0
	v_cndmask_b32_e64 v98, 0, 1, s[44:45]
	v_cmp_ne_u32_e64 s[40:41], 1, v98
	s_andn2_b64 vcc, exec, s[44:45]
	s_waitcnt vmcnt(15)
	ds_write_b128 v175, v[64:67]
	s_waitcnt vmcnt(14)
	ds_write_b128 v175, v[68:71] offset:4608
	s_waitcnt vmcnt(13)
	ds_write_b128 v175, v[72:75] offset:9216
	s_waitcnt vmcnt(12)
	ds_write_b128 v175, v[76:79] offset:13824
	s_waitcnt vmcnt(11)
	ds_write_b128 v175, v[80:83] offset:36864
	s_waitcnt vmcnt(10)
	ds_write_b128 v175, v[84:87] offset:41472
	s_waitcnt vmcnt(9)
	ds_write_b128 v175, v[88:91] offset:46080
	s_waitcnt vmcnt(8)
	ds_write_b128 v175, v[92:95] offset:50688
	s_cbranch_vccnz .LBB0_1355
	v_add_co_u32_e32 v68, vcc, 0x10000, v148
	global_load_dwordx4 v[64:67], v[148:149], off
	s_nop 0
	v_addc_co_u32_e32 v69, vcc, 0, v149, vcc
	v_add_co_u32_e32 v72, vcc, 0x20000, v148
	s_nop 1
	v_addc_co_u32_e32 v73, vcc, 0, v149, vcc
	v_add_co_u32_e32 v76, vcc, 0x30000, v148
	global_load_dwordx4 v[68:71], v[68:69], off
	global_load_dwordx4 v[72:75], v[72:73], off
	v_addc_co_u32_e32 v77, vcc, 0, v149, vcc
	v_add_co_u32_e32 v84, vcc, 0x10000, v146
	global_load_dwordx4 v[76:79], v[76:77], off
	s_nop 0
	global_load_dwordx4 v[80:83], v[146:147], off
	v_addc_co_u32_e32 v85, vcc, 0, v147, vcc
	v_add_co_u32_e32 v88, vcc, 0x20000, v146
	s_nop 1
	v_addc_co_u32_e32 v89, vcc, 0, v147, vcc
	v_add_co_u32_e32 v92, vcc, 0x30000, v146
	global_load_dwordx4 v[84:87], v[84:85], off
	s_nop 0
	global_load_dwordx4 v[88:91], v[88:89], off
	v_addc_co_u32_e32 v93, vcc, 0, v147, vcc
	global_load_dwordx4 v[92:95], v[92:93], off
.LBB0_1355:
	s_waitcnt lgkmcnt(0)
	s_barrier
	s_setprio 1
	ds_read_b128 v[212:215], v96 offset:36864
	ds_read_b128 v[216:219], v176
	ds_read_b128 v[220:223], v176 offset:4608
	ds_read_b128 v[224:227], v96 offset:41472
	ds_read_b128 v[228:231], v96 offset:36896
	ds_read_b128 v[244:247], v176 offset:32
	ds_read_b128 v[252:255], v176 offset:4640
	s_waitcnt lgkmcnt(5)
	v_mfma_f32_32x32x16_bf16 v[32:47], v[212:215], v[216:219], v[32:47]
	s_waitcnt lgkmcnt(4)
	v_mfma_f32_32x32x16_bf16 v[0:15], v[212:215], v[220:223], v[0:15]
	ds_read_b128 v[212:215], v96 offset:41504
	s_waitcnt lgkmcnt(4)
	v_mfma_f32_32x32x16_bf16 v[48:63], v[224:227], v[216:219], v[48:63]
	ds_read_b128 v[216:219], v96 offset:36928
	v_mfma_f32_32x32x16_bf16 v[16:31], v[224:227], v[220:223], v[16:31]
	ds_read_b128 v[224:227], v176 offset:64
	ds_read_b128 v[220:223], v176 offset:4672
	s_waitcnt lgkmcnt(5)
	v_mfma_f32_32x32x16_bf16 v[32:47], v[228:231], v[244:247], v[32:47]
	s_waitcnt lgkmcnt(4)
	v_mfma_f32_32x32x16_bf16 v[0:15], v[228:231], v[252:255], v[0:15]
	ds_read_b128 v[228:231], v96 offset:41536
	s_waitcnt lgkmcnt(4)
	v_mfma_f32_32x32x16_bf16 v[48:63], v[212:215], v[244:247], v[48:63]
	ds_read_b128 v[244:247], v96 offset:36960
	v_mfma_f32_32x32x16_bf16 v[16:31], v[212:215], v[252:255], v[16:31]
	ds_read_b128 v[212:215], v176 offset:96
	ds_read_b128 v[252:255], v176 offset:4704
	s_waitcnt lgkmcnt(5)
	v_mfma_f32_32x32x16_bf16 v[32:47], v[216:219], v[224:227], v[32:47]
	s_waitcnt lgkmcnt(4)
	v_mfma_f32_32x32x16_bf16 v[0:15], v[216:219], v[220:223], v[0:15]
	ds_read_b128 v[216:219], v96 offset:41568
	s_waitcnt lgkmcnt(4)
	v_mfma_f32_32x32x16_bf16 v[48:63], v[228:231], v[224:227], v[48:63]
	v_mfma_f32_32x32x16_bf16 v[16:31], v[228:231], v[220:223], v[16:31]
	s_waitcnt lgkmcnt(2)
	v_mfma_f32_32x32x16_bf16 v[32:47], v[244:247], v[212:215], v[32:47]
	s_waitcnt lgkmcnt(1)
	v_mfma_f32_32x32x16_bf16 v[0:15], v[244:247], v[252:255], v[0:15]
	s_waitcnt lgkmcnt(0)
	v_mfma_f32_32x32x16_bf16 v[48:63], v[216:219], v[212:215], v[48:63]
	v_mfma_f32_32x32x16_bf16 v[16:31], v[216:219], v[252:255], v[16:31]
	s_setprio 0
	v_readlane_b32 s56, v249, 62
	s_and_b64 vcc, exec, s[40:41]
	v_readlane_b32 s57, v249, 63
	s_mov_b64 s[16:17], s[82:83]
	s_waitcnt vmcnt(7)
	ds_write_b128 v175, v[100:103] offset:18432
	s_waitcnt vmcnt(6)
	ds_write_b128 v175, v[104:107] offset:23040
	s_waitcnt vmcnt(5)
	ds_write_b128 v175, v[108:111] offset:27648
	s_waitcnt vmcnt(4)
	ds_write_b128 v175, v[112:115] offset:32256
	s_waitcnt vmcnt(3)
	ds_write_b128 v175, v[116:119] offset:55296
	s_waitcnt vmcnt(2)
	ds_write_b128 v175, v[124:127] offset:59904
	s_waitcnt vmcnt(1)
	ds_write_b128 v175, v[120:123] offset:64512
	s_waitcnt vmcnt(0)
	ds_write_b128 v177, v[128:131] offset:13824
	s_cbranch_vccnz .LBB0_1357
	v_add_co_u32_e32 v98, vcc, 0x10000, v148
	global_load_dwordx4 v[100:103], v[148:149], off offset:128
	s_nop 0
	v_addc_co_u32_e32 v99, vcc, 0, v149, vcc
	v_add_co_u32_e32 v108, vcc, 0x20000, v148
	s_nop 1
	v_addc_co_u32_e32 v109, vcc, 0, v149, vcc
	global_load_dwordx4 v[104:107], v[98:99], off offset:128
	global_load_dwordx4 v[108:111], v[108:109], off offset:128
	v_add_co_u32_e32 v98, vcc, 0x30000, v148
	s_nop 1
	v_addc_co_u32_e32 v99, vcc, 0, v149, vcc
	global_load_dwordx4 v[112:115], v[98:99], off offset:128
	global_load_dwordx4 v[116:119], v[146:147], off offset:128
	v_add_co_u32_e32 v98, vcc, 0x10000, v146
	s_nop 1
	v_addc_co_u32_e32 v99, vcc, 0, v147, vcc
	v_add_co_u32_e32 v120, vcc, 0x20000, v146
	s_nop 1
	v_addc_co_u32_e32 v121, vcc, 0, v147, vcc
	global_load_dwordx4 v[124:127], v[98:99], off offset:128
	s_nop 0
	global_load_dwordx4 v[120:123], v[120:121], off offset:128
	v_add_co_u32_e32 v98, vcc, 0x30000, v146
	s_nop 1
	v_addc_co_u32_e32 v99, vcc, 0, v147, vcc
	global_load_dwordx4 v[128:131], v[98:99], off offset:128

.LBB0_1416:
	v_mad_i64_i32 v[2:3], s[38:39], v1, s18, 0
	s_add_u32 s38, s56, s6
	s_addc_u32 s39, s57, s7
	s_and_b64 s[6:7], s[44:45], exec
	v_readlane_b32 s9, v249, 35
	s_cselect_b32 s7, s39, 0
	s_cselect_b32 s6, s38, 0
	s_add_u32 s38, s9, s12
	v_readlane_b32 s9, v249, 36
	s_addc_u32 s39, s9, s13
	s_and_b64 s[12:13], s[44:45], exec
	s_cselect_b32 s13, s39, 0
	s_cselect_b32 s12, s38, 0
	v_lshl_add_u64 v[4:5], s[6:7], 0, v[2:3]
	v_lshl_add_u64 v[2:3], s[12:13], 0, v[2:3]
	v_lshl_add_u64 v[170:171], v[2:3], 0, v[96:97]
	v_lshrrev_b32_e32 v1, 1, v0
	v_and_b32_e32 v2, 31, v0
	v_and_or_b32 v1, v1, s81, v2
	v_lshrrev_b32_e32 v2, 2, v0
	v_and_b32_e32 v2, 8, v2
	v_and_b32_e32 v0, 0x5f, v0
	v_lshl_add_u64 v[172:173], v[4:5], 0, v[96:97]
	v_mad_u64_u32 v[4:5], s[6:7], v1, s84, v[2:3]
	v_mad_u32_u24 v0, v0, s84, v2
	v_lshl_add_u32 v210, v4, 1, 0
	v_lshl_add_u32 v96, v0, 1, 0
	v_add_u32_e32 v211, 0xd800, v209
	s_setprio 1
	ds_read_b128 v[212:215], v96 offset:36864
	ds_read_b128 v[216:219], v210
	ds_read_b128 v[220:223], v210 offset:4608
	ds_read_b128 v[224:227], v96 offset:36896
	ds_read_b128 v[228:231], v210 offset:32
	ds_read_b128 v[244:247], v210 offset:4640
	ds_read_b128 v[252:255], v96 offset:41472
	s_waitcnt lgkmcnt(5)
	v_mfma_f32_32x32x16_bf16 v[48:63], v[212:215], v[216:219], 0
	s_waitcnt lgkmcnt(4)
	v_mfma_f32_32x32x16_bf16 v[32:47], v[212:215], v[220:223], 0
	ds_read_b128 v[212:215], v96 offset:41504
	s_waitcnt lgkmcnt(3)
	v_mfma_f32_32x32x16_bf16 v[48:63], v[224:227], v[228:231], v[48:63]
	s_waitcnt lgkmcnt(2)
	v_mfma_f32_32x32x16_bf16 v[32:47], v[224:227], v[244:247], v[32:47]
	ds_read_b128 v[224:227], v96 offset:36928
	s_waitcnt lgkmcnt(2)
	v_mfma_f32_32x32x16_bf16 v[16:31], v[252:255], v[216:219], 0
	ds_read_b128 v[216:219], v210 offset:64
	v_mfma_f32_32x32x16_bf16 v[0:15], v[252:255], v[220:223], 0
	ds_read_b128 v[252:255], v210 offset:4672
	ds_read_b128 v[220:223], v96 offset:41536
	s_waitcnt lgkmcnt(4)
	v_mfma_f32_32x32x16_bf16 v[16:31], v[212:215], v[228:231], v[16:31]
	ds_read_b128 v[228:231], v96 offset:36960
	v_mfma_f32_32x32x16_bf16 v[0:15], v[212:215], v[244:247], v[0:15]
	ds_read_b128 v[212:215], v210 offset:96
	ds_read_b128 v[244:247], v210 offset:4704
	s_waitcnt lgkmcnt(5)
	v_mfma_f32_32x32x16_bf16 v[48:63], v[224:227], v[216:219], v[48:63]
	v_add_co_u32_e32 v150, vcc, s19, v148
	s_waitcnt vmcnt(15)
	ds_write_b128 v209, v[100:103] offset:18432
	s_waitcnt vmcnt(14)
	ds_write_b128 v209, v[104:107] offset:23040
	s_waitcnt lgkmcnt(6)
	v_mfma_f32_32x32x16_bf16 v[32:47], v[224:227], v[252:255], v[32:47]
	ds_read_b128 v[224:227], v96 offset:41568
	s_waitcnt vmcnt(13)
	ds_write_b128 v209, v[108:111] offset:27648
	s_waitcnt vmcnt(12)
	ds_write_b128 v209, v[116:119] offset:32256
	s_waitcnt vmcnt(11)
	s_waitcnt lgkmcnt(8)
	v_mfma_f32_32x32x16_bf16 v[16:31], v[220:223], v[216:219], v[16:31]
	ds_write_b128 v209, v[112:115] offset:55296
	s_waitcnt vmcnt(10)
	ds_write_b128 v209, v[120:123] offset:59904
	s_waitcnt vmcnt(9)
	ds_write_b128 v209, v[124:127] offset:64512
	v_mfma_f32_32x32x16_bf16 v[0:15], v[220:223], v[252:255], v[0:15]
	s_waitcnt vmcnt(8)
	ds_write_b128 v211, v[128:131] offset:13824
	v_addc_co_u32_e32 v151, vcc, 0, v149, vcc
	v_add_co_u32_e32 v152, vcc, s20, v148
	s_waitcnt lgkmcnt(10)
	v_mfma_f32_32x32x16_bf16 v[48:63], v[228:231], v[212:215], v[48:63]
	global_load_dwordx4 v[98:101], v[148:149], off offset:384
	global_load_dwordx4 v[102:105], v[150:151], off offset:384
	v_addc_co_u32_e32 v153, vcc, 0, v149, vcc
	v_add_co_u32_e32 v154, vcc, s21, v148
	global_load_dwordx4 v[106:109], v[152:153], off offset:384
	s_waitcnt lgkmcnt(9)
	v_mfma_f32_32x32x16_bf16 v[32:47], v[228:231], v[244:247], v[32:47]
	s_nop 0
	v_addc_co_u32_e32 v155, vcc, 0, v149, vcc
	v_add_co_u32_e32 v156, vcc, s19, v146
	global_load_dwordx4 v[110:113], v[154:155], off offset:384
	global_load_dwordx4 v[114:117], v[146:147], off offset:384
	s_waitcnt lgkmcnt(6)
	v_mfma_f32_32x32x16_bf16 v[16:31], v[224:227], v[212:215], v[16:31]
	v_addc_co_u32_e32 v157, vcc, 0, v147, vcc
	v_add_co_u32_e32 v158, vcc, s20, v146
	global_load_dwordx4 v[118:121], v[156:157], off offset:384
	s_nop 0
	v_addc_co_u32_e32 v159, vcc, 0, v147, vcc
	v_mfma_f32_32x32x16_bf16 v[0:15], v[224:227], v[244:247], v[0:15]
	v_add_co_u32_e32 v160, vcc, s21, v146
	global_load_dwordx4 v[122:125], v[158:159], off offset:384
	s_nop 0
	v_addc_co_u32_e32 v161, vcc, 0, v147, vcc
	global_load_dwordx4 v[130:133], v[160:161], off offset:384
	s_setprio 0
	s_waitcnt lgkmcnt(0)
	s_barrier
	s_setprio 1
	ds_read_b128 v[212:215], v96 offset:55296
	ds_read_b128 v[216:219], v210 offset:18432
	ds_read_b128 v[220:223], v210 offset:23040
	ds_read_b128 v[224:227], v96 offset:59904
	ds_read_b128 v[228:231], v96 offset:55328
	ds_read_b128 v[244:247], v210 offset:18464
	ds_read_b128 v[252:255], v210 offset:23072
	s_waitcnt lgkmcnt(5)
	v_mfma_f32_32x32x16_bf16 v[48:63], v[212:215], v[216:219], v[48:63]
	s_waitcnt lgkmcnt(4)
	v_mfma_f32_32x32x16_bf16 v[32:47], v[212:215], v[220:223], v[32:47]
	ds_read_b128 v[212:215], v96 offset:59936
	s_waitcnt lgkmcnt(4)
	v_mfma_f32_32x32x16_bf16 v[16:31], v[224:227], v[216:219], v[16:31]
	ds_read_b128 v[216:219], v96 offset:55360
	v_mfma_f32_32x32x16_bf16 v[0:15], v[224:227], v[220:223], v[0:15]
	ds_read_b128 v[224:227], v210 offset:18496
	ds_read_b128 v[220:223], v210 offset:23104
	s_waitcnt lgkmcnt(5)
	v_mfma_f32_32x32x16_bf16 v[48:63], v[228:231], v[244:247], v[48:63]
	s_waitcnt lgkmcnt(4)
	v_mfma_f32_32x32x16_bf16 v[32:47], v[228:231], v[252:255], v[32:47]
	ds_read_b128 v[228:231], v96 offset:59968
	s_waitcnt lgkmcnt(4)
	v_mfma_f32_32x32x16_bf16 v[16:31], v[212:215], v[244:247], v[16:31]
	ds_read_b128 v[244:247], v96 offset:55392
	v_mfma_f32_32x32x16_bf16 v[0:15], v[212:215], v[252:255], v[0:15]
	ds_read_b128 v[212:215], v210 offset:18528
	ds_read_b128 v[252:255], v210 offset:23136
	s_waitcnt lgkmcnt(5)
	v_mfma_f32_32x32x16_bf16 v[48:63], v[216:219], v[224:227], v[48:63]
	s_waitcnt vmcnt(15)
	ds_write_b128 v209, v[64:67]
	global_load_dwordx4 v[64:67], v[148:149], off offset:512
	s_waitcnt lgkmcnt(5)
	v_mfma_f32_32x32x16_bf16 v[32:47], v[216:219], v[220:223], v[32:47]
	ds_read_b128 v[216:219], v96 offset:60000
	s_waitcnt vmcnt(15)
	ds_write_b128 v209, v[68:71] offset:4608
	s_waitcnt vmcnt(14)
	ds_write_b128 v209, v[72:75] offset:9216
	s_waitcnt lgkmcnt(7)
	v_mfma_f32_32x32x16_bf16 v[16:31], v[228:231], v[224:227], v[16:31]
	global_load_dwordx4 v[72:75], v[150:151], off offset:512
	s_waitcnt vmcnt(14)
	ds_write_b128 v209, v[76:79] offset:13824
	v_mfma_f32_32x32x16_bf16 v[0:15], v[228:231], v[220:223], v[0:15]
	global_load_dwordx4 v[76:79], v[152:153], off offset:512
	s_waitcnt vmcnt(14)
	ds_write_b128 v209, v[80:83] offset:36864
	s_waitcnt lgkmcnt(7)
	v_mfma_f32_32x32x16_bf16 v[48:63], v[244:247], v[212:215], v[48:63]
	global_load_dwordx4 v[80:83], v[154:155], off offset:512
	global_load_dwordx4 v[126:129], v[146:147], off offset:512
	s_waitcnt lgkmcnt(6)
	v_mfma_f32_32x32x16_bf16 v[32:47], v[244:247], v[252:255], v[32:47]
	s_waitcnt vmcnt(15)
	ds_write_b128 v209, v[84:87] offset:41472
	global_load_dwordx4 v[134:137], v[156:157], off offset:512
	s_waitcnt lgkmcnt(5)
	v_mfma_f32_32x32x16_bf16 v[16:31], v[216:219], v[212:215], v[16:31]
	s_waitcnt vmcnt(15)
	ds_write_b128 v209, v[88:91] offset:46080
	global_load_dwordx4 v[138:141], v[158:159], off offset:512
	v_mfma_f32_32x32x16_bf16 v[0:15], v[216:219], v[252:255], v[0:15]
	s_waitcnt vmcnt(15)
	ds_write_b128 v209, v[92:95] offset:50688
	global_load_dwordx4 v[142:145], v[160:161], off offset:512
	s_setprio 0
	s_waitcnt lgkmcnt(0)
	s_barrier
	s_setprio 1
	ds_read_b128 v[212:215], v96 offset:36864
	ds_read_b128 v[216:219], v210
	ds_read_b128 v[220:223], v210 offset:4608
	ds_read_b128 v[224:227], v96 offset:41472
	ds_read_b128 v[228:231], v96 offset:36896
	ds_read_b128 v[244:247], v210 offset:32
	ds_read_b128 v[252:255], v210 offset:4640
	s_waitcnt lgkmcnt(5)
	v_mfma_f32_32x32x16_bf16 v[48:63], v[212:215], v[216:219], v[48:63]
	s_waitcnt lgkmcnt(4)
	v_mfma_f32_32x32x16_bf16 v[32:47], v[212:215], v[220:223], v[32:47]
	ds_read_b128 v[212:215], v96 offset:41504
	s_waitcnt lgkmcnt(4)
	v_mfma_f32_32x32x16_bf16 v[16:31], v[224:227], v[216:219], v[16:31]
	ds_read_b128 v[216:219], v96 offset:36928
	v_mfma_f32_32x32x16_bf16 v[0:15], v[224:227], v[220:223], v[0:15]
	ds_read_b128 v[224:227], v210 offset:64
	ds_read_b128 v[220:223], v210 offset:4672
	s_waitcnt lgkmcnt(5)
	v_mfma_f32_32x32x16_bf16 v[48:63], v[228:231], v[244:247], v[48:63]
	s_waitcnt lgkmcnt(4)
	v_mfma_f32_32x32x16_bf16 v[32:47], v[228:231], v[252:255], v[32:47]
	ds_read_b128 v[228:231], v96 offset:41536
	s_waitcnt lgkmcnt(4)
	v_mfma_f32_32x32x16_bf16 v[16:31], v[212:215], v[244:247], v[16:31]
	ds_read_b128 v[244:247], v96 offset:36960
	v_mfma_f32_32x32x16_bf16 v[0:15], v[212:215], v[252:255], v[0:15]
	ds_read_b128 v[212:215], v210 offset:96
	ds_read_b128 v[252:255], v210 offset:4704
	s_waitcnt lgkmcnt(5)
	v_mfma_f32_32x32x16_bf16 v[48:63], v[216:219], v[224:227], v[48:63]
	s_waitcnt vmcnt(15)
	ds_write_b128 v209, v[98:101] offset:18432
	global_load_dwordx4 v[68:71], v[148:149], off offset:640
	s_waitcnt lgkmcnt(5)
	v_mfma_f32_32x32x16_bf16 v[32:47], v[216:219], v[220:223], v[32:47]
	ds_read_b128 v[216:219], v96 offset:41568
	s_waitcnt vmcnt(15)
	ds_write_b128 v209, v[102:105] offset:23040
	global_load_dwordx4 v[84:87], v[150:151], off offset:640
	s_waitcnt lgkmcnt(6)
	v_mfma_f32_32x32x16_bf16 v[16:31], v[228:231], v[224:227], v[16:31]
	s_waitcnt vmcnt(15)
	ds_write_b128 v209, v[106:109] offset:27648
	global_load_dwordx4 v[88:91], v[152:153], off offset:640
	v_mfma_f32_32x32x16_bf16 v[0:15], v[228:231], v[220:223], v[0:15]
	s_waitcnt vmcnt(15)
	ds_write_b128 v209, v[110:113] offset:32256
	global_load_dwordx4 v[92:95], v[154:155], off offset:640
	s_waitcnt lgkmcnt(6)
	v_mfma_f32_32x32x16_bf16 v[48:63], v[244:247], v[212:215], v[48:63]
	s_waitcnt vmcnt(15)
	ds_write_b128 v209, v[114:117] offset:55296
	global_load_dwordx4 v[98:101], v[146:147], off offset:640
	s_waitcnt lgkmcnt(6)
	v_mfma_f32_32x32x16_bf16 v[32:47], v[244:247], v[252:255], v[32:47]
	s_waitcnt vmcnt(15)
	ds_write_b128 v209, v[118:121] offset:59904
	global_load_dwordx4 v[106:109], v[156:157], off offset:640
	s_waitcnt lgkmcnt(5)
	v_mfma_f32_32x32x16_bf16 v[16:31], v[216:219], v[212:215], v[16:31]
	s_waitcnt vmcnt(15)
	ds_write_b128 v209, v[122:125] offset:64512
	global_load_dwordx4 v[110:113], v[158:159], off offset:640
	v_mfma_f32_32x32x16_bf16 v[0:15], v[216:219], v[252:255], v[0:15]
	s_waitcnt vmcnt(15)
	ds_write_b128 v211, v[130:133] offset:13824
	global_load_dwordx4 v[114:117], v[160:161], off offset:640
	s_setprio 0
	s_waitcnt lgkmcnt(0)
	s_barrier
	s_setprio 1
	ds_read_b128 v[212:215], v96 offset:55296
	ds_read_b128 v[216:219], v210 offset:18432
	ds_read_b128 v[220:223], v210 offset:23040
	ds_read_b128 v[224:227], v96 offset:59904
	ds_read_b128 v[228:231], v96 offset:55328
	ds_read_b128 v[244:247], v210 offset:18464
	ds_read_b128 v[252:255], v210 offset:23072
	s_waitcnt lgkmcnt(5)
	v_mfma_f32_32x32x16_bf16 v[48:63], v[212:215], v[216:219], v[48:63]
	s_waitcnt lgkmcnt(4)
	v_mfma_f32_32x32x16_bf16 v[32:47], v[212:215], v[220:223], v[32:47]
	ds_read_b128 v[212:215], v96 offset:59936
	s_waitcnt lgkmcnt(4)
	v_mfma_f32_32x32x16_bf16 v[16:31], v[224:227], v[216:219], v[16:31]
	ds_read_b128 v[216:219], v96 offset:55360
	v_mfma_f32_32x32x16_bf16 v[0:15], v[224:227], v[220:223], v[0:15]
	ds_read_b128 v[224:227], v210 offset:18496
	ds_read_b128 v[220:223], v210 offset:23104
	s_waitcnt lgkmcnt(5)
	v_mfma_f32_32x32x16_bf16 v[48:63], v[228:231], v[244:247], v[48:63]
	s_waitcnt lgkmcnt(4)
	v_mfma_f32_32x32x16_bf16 v[32:47], v[228:231], v[252:255], v[32:47]
	ds_read_b128 v[228:231], v96 offset:59968
	s_waitcnt lgkmcnt(4)
	v_mfma_f32_32x32x16_bf16 v[16:31], v[212:215], v[244:247], v[16:31]
	ds_read_b128 v[244:247], v96 offset:55392
	v_mfma_f32_32x32x16_bf16 v[0:15], v[212:215], v[252:255], v[0:15]
	ds_read_b128 v[212:215], v210 offset:18528
	ds_read_b128 v[252:255], v210 offset:23136
	s_waitcnt lgkmcnt(5)
	v_mfma_f32_32x32x16_bf16 v[48:63], v[216:219], v[224:227], v[48:63]
	s_waitcnt vmcnt(15)
	ds_write_b128 v209, v[64:67]
	global_load_dwordx4 v[64:67], v[148:149], off offset:768
	s_waitcnt lgkmcnt(5)
	v_mfma_f32_32x32x16_bf16 v[32:47], v[216:219], v[220:223], v[32:47]
	ds_read_b128 v[216:219], v96 offset:60000
	s_waitcnt vmcnt(15)
	ds_write_b128 v209, v[72:75] offset:4608
	global_load_dwordx4 v[72:75], v[150:151], off offset:768
	s_waitcnt lgkmcnt(6)
	v_mfma_f32_32x32x16_bf16 v[16:31], v[228:231], v[224:227], v[16:31]
	s_waitcnt vmcnt(15)
	ds_write_b128 v209, v[76:79] offset:9216
	global_load_dwordx4 v[76:79], v[152:153], off offset:768
	v_mfma_f32_32x32x16_bf16 v[0:15], v[228:231], v[220:223], v[0:15]
	s_waitcnt vmcnt(15)
	ds_write_b128 v209, v[80:83] offset:13824
	global_load_dwordx4 v[80:83], v[154:155], off offset:768
	s_waitcnt lgkmcnt(6)
	v_mfma_f32_32x32x16_bf16 v[48:63], v[244:247], v[212:215], v[48:63]
	s_waitcnt vmcnt(15)
	ds_write_b128 v209, v[126:129] offset:36864
	global_load_dwordx4 v[102:105], v[146:147], off offset:768
	s_waitcnt lgkmcnt(6)
	v_mfma_f32_32x32x16_bf16 v[32:47], v[244:247], v[252:255], v[32:47]
	s_waitcnt vmcnt(15)
	ds_write_b128 v209, v[134:137] offset:41472
	global_load_dwordx4 v[118:121], v[156:157], off offset:768
	s_waitcnt lgkmcnt(5)
	v_mfma_f32_32x32x16_bf16 v[16:31], v[216:219], v[212:215], v[16:31]
	s_waitcnt vmcnt(15)
	ds_write_b128 v209, v[138:141] offset:46080
	global_load_dwordx4 v[122:125], v[158:159], off offset:768
	v_mfma_f32_32x32x16_bf16 v[0:15], v[216:219], v[252:255], v[0:15]
	s_waitcnt vmcnt(15)
	ds_write_b128 v209, v[142:145] offset:50688
	global_load_dwordx4 v[126:129], v[160:161], off offset:768
	s_setprio 0
	s_waitcnt lgkmcnt(0)
	s_barrier
	s_setprio 1
	ds_read_b128 v[212:215], v96 offset:36864
	ds_read_b128 v[216:219], v210
	ds_read_b128 v[220:223], v210 offset:4608
	ds_read_b128 v[224:227], v96 offset:41472
	ds_read_b128 v[228:231], v96 offset:36896
	ds_read_b128 v[244:247], v210 offset:32
	ds_read_b128 v[252:255], v210 offset:4640
	s_waitcnt lgkmcnt(5)
	v_mfma_f32_32x32x16_bf16 v[48:63], v[212:215], v[216:219], v[48:63]
	s_waitcnt lgkmcnt(4)
	v_mfma_f32_32x32x16_bf16 v[32:47], v[212:215], v[220:223], v[32:47]
	ds_read_b128 v[212:215], v96 offset:41504
	s_waitcnt lgkmcnt(4)
	v_mfma_f32_32x32x16_bf16 v[16:31], v[224:227], v[216:219], v[16:31]
	ds_read_b128 v[216:219], v96 offset:36928
	v_mfma_f32_32x32x16_bf16 v[0:15], v[224:227], v[220:223], v[0:15]
	ds_read_b128 v[224:227], v210 offset:64
	ds_read_b128 v[220:223], v210 offset:4672
	s_waitcnt lgkmcnt(5)
	v_mfma_f32_32x32x16_bf16 v[48:63], v[228:231], v[244:247], v[48:63]
	s_waitcnt lgkmcnt(4)
	v_mfma_f32_32x32x16_bf16 v[32:47], v[228:231], v[252:255], v[32:47]
	ds_read_b128 v[228:231], v96 offset:41536
	s_waitcnt lgkmcnt(4)
	v_mfma_f32_32x32x16_bf16 v[16:31], v[212:215], v[244:247], v[16:31]
	ds_read_b128 v[244:247], v96 offset:36960
	v_mfma_f32_32x32x16_bf16 v[0:15], v[212:215], v[252:255], v[0:15]
	ds_read_b128 v[212:215], v210 offset:96
	ds_read_b128 v[252:255], v210 offset:4704
	s_waitcnt lgkmcnt(5)
	v_mfma_f32_32x32x16_bf16 v[48:63], v[216:219], v[224:227], v[48:63]
	s_waitcnt vmcnt(15)
	ds_write_b128 v209, v[68:71] offset:18432
	global_load_dwordx4 v[68:71], v[148:149], off offset:896
	s_waitcnt lgkmcnt(5)
	v_mfma_f32_32x32x16_bf16 v[32:47], v[216:219], v[220:223], v[32:47]
	ds_read_b128 v[216:219], v96 offset:41568
	s_waitcnt vmcnt(15)
	ds_write_b128 v209, v[84:87] offset:23040
	global_load_dwordx4 v[84:87], v[150:151], off offset:896
	s_waitcnt lgkmcnt(6)
	v_mfma_f32_32x32x16_bf16 v[16:31], v[228:231], v[224:227], v[16:31]
	s_waitcnt vmcnt(15)
	ds_write_b128 v209, v[88:91] offset:27648
	global_load_dwordx4 v[88:91], v[152:153], off offset:896
	v_mfma_f32_32x32x16_bf16 v[0:15], v[228:231], v[220:223], v[0:15]
	s_waitcnt vmcnt(15)
	ds_write_b128 v209, v[92:95] offset:32256
	global_load_dwordx4 v[92:95], v[154:155], off offset:896
	s_waitcnt lgkmcnt(6)
	v_mfma_f32_32x32x16_bf16 v[48:63], v[244:247], v[212:215], v[48:63]
	s_waitcnt vmcnt(15)
	ds_write_b128 v209, v[98:101] offset:55296
	global_load_dwordx4 v[98:101], v[146:147], off offset:896
	s_waitcnt lgkmcnt(6)
	v_mfma_f32_32x32x16_bf16 v[32:47], v[244:247], v[252:255], v[32:47]
	s_waitcnt vmcnt(15)
	ds_write_b128 v209, v[106:109] offset:59904
	global_load_dwordx4 v[106:109], v[156:157], off offset:896
	s_waitcnt lgkmcnt(5)
	v_mfma_f32_32x32x16_bf16 v[16:31], v[216:219], v[212:215], v[16:31]
	s_waitcnt vmcnt(15)
	ds_write_b128 v209, v[110:113] offset:64512
	global_load_dwordx4 v[110:113], v[158:159], off offset:896
	v_mfma_f32_32x32x16_bf16 v[0:15], v[216:219], v[252:255], v[0:15]
	s_waitcnt vmcnt(15)
	ds_write_b128 v211, v[114:117] offset:13824
	global_load_dwordx4 v[114:117], v[160:161], off offset:896
	s_setprio 0
	s_waitcnt lgkmcnt(0)
	s_barrier
	s_setprio 1
	ds_read_b128 v[212:215], v96 offset:55296
	ds_read_b128 v[216:219], v210 offset:18432
	ds_read_b128 v[220:223], v210 offset:23040
	ds_read_b128 v[224:227], v96 offset:59904
	ds_read_b128 v[228:231], v96 offset:55328
	ds_read_b128 v[244:247], v210 offset:18464
	ds_read_b128 v[252:255], v210 offset:23072
	s_waitcnt lgkmcnt(5)
	v_mfma_f32_32x32x16_bf16 v[48:63], v[212:215], v[216:219], v[48:63]
	s_waitcnt lgkmcnt(4)
	v_mfma_f32_32x32x16_bf16 v[32:47], v[212:215], v[220:223], v[32:47]
	ds_read_b128 v[212:215], v96 offset:59936
	s_waitcnt lgkmcnt(4)
	v_mfma_f32_32x32x16_bf16 v[16:31], v[224:227], v[216:219], v[16:31]
	ds_read_b128 v[216:219], v96 offset:55360
	v_mfma_f32_32x32x16_bf16 v[0:15], v[224:227], v[220:223], v[0:15]
	ds_read_b128 v[224:227], v210 offset:18496
	ds_read_b128 v[220:223], v210 offset:23104
	s_waitcnt lgkmcnt(5)
	v_mfma_f32_32x32x16_bf16 v[48:63], v[228:231], v[244:247], v[48:63]
	s_waitcnt lgkmcnt(4)
	v_mfma_f32_32x32x16_bf16 v[32:47], v[228:231], v[252:255], v[32:47]
	ds_read_b128 v[228:231], v96 offset:59968
	s_waitcnt lgkmcnt(4)
	v_mfma_f32_32x32x16_bf16 v[16:31], v[212:215], v[244:247], v[16:31]
	ds_read_b128 v[244:247], v96 offset:55392
	v_mfma_f32_32x32x16_bf16 v[0:15], v[212:215], v[252:255], v[0:15]
	ds_read_b128 v[212:215], v210 offset:18528
	ds_read_b128 v[252:255], v210 offset:23136
	s_waitcnt lgkmcnt(5)
	v_mfma_f32_32x32x16_bf16 v[48:63], v[216:219], v[224:227], v[48:63]
	s_waitcnt vmcnt(15)
	ds_write_b128 v209, v[64:67]
	global_load_dwordx4 v[64:67], v[148:149], off offset:1024
	s_waitcnt lgkmcnt(5)
	v_mfma_f32_32x32x16_bf16 v[32:47], v[216:219], v[220:223], v[32:47]
	ds_read_b128 v[216:219], v96 offset:60000
	s_waitcnt vmcnt(15)
	ds_write_b128 v209, v[72:75] offset:4608
	global_load_dwordx4 v[72:75], v[150:151], off offset:1024
	s_waitcnt lgkmcnt(6)
	v_mfma_f32_32x32x16_bf16 v[16:31], v[228:231], v[224:227], v[16:31]
	s_waitcnt vmcnt(15)
	ds_write_b128 v209, v[76:79] offset:9216
	global_load_dwordx4 v[76:79], v[152:153], off offset:1024
	v_mfma_f32_32x32x16_bf16 v[0:15], v[228:231], v[220:223], v[0:15]
	s_waitcnt vmcnt(15)
	ds_write_b128 v209, v[80:83] offset:13824
	global_load_dwordx4 v[80:83], v[154:155], off offset:1024
	s_waitcnt lgkmcnt(6)
	v_mfma_f32_32x32x16_bf16 v[48:63], v[244:247], v[212:215], v[48:63]
	s_waitcnt vmcnt(15)
	ds_write_b128 v209, v[102:105] offset:36864
	global_load_dwordx4 v[102:105], v[146:147], off offset:1024
	s_waitcnt lgkmcnt(6)
	v_mfma_f32_32x32x16_bf16 v[32:47], v[244:247], v[252:255], v[32:47]
	s_waitcnt vmcnt(15)
	ds_write_b128 v209, v[118:121] offset:41472
	global_load_dwordx4 v[118:121], v[156:157], off offset:1024
	s_waitcnt lgkmcnt(5)
	v_mfma_f32_32x32x16_bf16 v[16:31], v[216:219], v[212:215], v[16:31]
	s_waitcnt vmcnt(15)
	ds_write_b128 v209, v[122:125] offset:46080
	global_load_dwordx4 v[122:125], v[158:159], off offset:1024
	v_mfma_f32_32x32x16_bf16 v[0:15], v[216:219], v[252:255], v[0:15]
	s_waitcnt vmcnt(15)
	ds_write_b128 v209, v[126:129] offset:50688
	global_load_dwordx4 v[126:129], v[160:161], off offset:1024
	s_setprio 0
	s_waitcnt lgkmcnt(0)
	s_barrier
	s_setprio 1
	ds_read_b128 v[212:215], v96 offset:36864
	ds_read_b128 v[216:219], v210
	ds_read_b128 v[220:223], v210 offset:4608
	ds_read_b128 v[224:227], v96 offset:41472
	ds_read_b128 v[228:231], v96 offset:36896
	ds_read_b128 v[244:247], v210 offset:32
	ds_read_b128 v[252:255], v210 offset:4640
	s_waitcnt lgkmcnt(5)
	v_mfma_f32_32x32x16_bf16 v[48:63], v[212:215], v[216:219], v[48:63]
	s_waitcnt lgkmcnt(4)
	v_mfma_f32_32x32x16_bf16 v[32:47], v[212:215], v[220:223], v[32:47]
	ds_read_b128 v[212:215], v96 offset:41504
	s_waitcnt lgkmcnt(4)
	v_mfma_f32_32x32x16_bf16 v[16:31], v[224:227], v[216:219], v[16:31]
	ds_read_b128 v[216:219], v96 offset:36928
	v_mfma_f32_32x32x16_bf16 v[0:15], v[224:227], v[220:223], v[0:15]
	ds_read_b128 v[224:227], v210 offset:64
	ds_read_b128 v[220:223], v210 offset:4672
	s_waitcnt lgkmcnt(5)
	v_mfma_f32_32x32x16_bf16 v[48:63], v[228:231], v[244:247], v[48:63]
	s_waitcnt lgkmcnt(4)
	v_mfma_f32_32x32x16_bf16 v[32:47], v[228:231], v[252:255], v[32:47]
	ds_read_b128 v[228:231], v96 offset:41536
	s_waitcnt lgkmcnt(4)
	v_mfma_f32_32x32x16_bf16 v[16:31], v[212:215], v[244:247], v[16:31]
	ds_read_b128 v[244:247], v96 offset:36960
	v_mfma_f32_32x32x16_bf16 v[0:15], v[212:215], v[252:255], v[0:15]
	ds_read_b128 v[212:215], v210 offset:96
	ds_read_b128 v[252:255], v210 offset:4704
	s_waitcnt lgkmcnt(5)
	v_mfma_f32_32x32x16_bf16 v[48:63], v[216:219], v[224:227], v[48:63]
	s_waitcnt vmcnt(15)
	ds_write_b128 v209, v[68:71] offset:18432
	global_load_dwordx4 v[68:71], v[148:149], off offset:1152
	s_waitcnt lgkmcnt(5)
	v_mfma_f32_32x32x16_bf16 v[32:47], v[216:219], v[220:223], v[32:47]
	ds_read_b128 v[216:219], v96 offset:41568
	s_waitcnt vmcnt(15)
	ds_write_b128 v209, v[84:87] offset:23040
	global_load_dwordx4 v[84:87], v[150:151], off offset:1152
	s_waitcnt lgkmcnt(6)
	v_mfma_f32_32x32x16_bf16 v[16:31], v[228:231], v[224:227], v[16:31]
	s_waitcnt vmcnt(15)
	ds_write_b128 v209, v[88:91] offset:27648
	global_load_dwordx4 v[88:91], v[152:153], off offset:1152
	v_mfma_f32_32x32x16_bf16 v[0:15], v[228:231], v[220:223], v[0:15]
	s_waitcnt vmcnt(15)
	ds_write_b128 v209, v[92:95] offset:32256
	global_load_dwordx4 v[92:95], v[154:155], off offset:1152
	s_waitcnt lgkmcnt(6)
	v_mfma_f32_32x32x16_bf16 v[48:63], v[244:247], v[212:215], v[48:63]
	s_waitcnt vmcnt(15)
	ds_write_b128 v209, v[98:101] offset:55296
	global_load_dwordx4 v[98:101], v[146:147], off offset:1152
	s_waitcnt lgkmcnt(6)
	v_mfma_f32_32x32x16_bf16 v[32:47], v[244:247], v[252:255], v[32:47]
	s_waitcnt vmcnt(15)
	ds_write_b128 v209, v[106:109] offset:59904
	global_load_dwordx4 v[106:109], v[156:157], off offset:1152
	s_waitcnt lgkmcnt(5)
	v_mfma_f32_32x32x16_bf16 v[16:31], v[216:219], v[212:215], v[16:31]
	s_waitcnt vmcnt(15)
	ds_write_b128 v209, v[110:113] offset:64512
	global_load_dwordx4 v[110:113], v[158:159], off offset:1152
	v_mfma_f32_32x32x16_bf16 v[0:15], v[216:219], v[252:255], v[0:15]
	s_waitcnt vmcnt(15)
	ds_write_b128 v211, v[114:117] offset:13824
	global_load_dwordx4 v[114:117], v[160:161], off offset:1152
	s_setprio 0
	s_waitcnt lgkmcnt(0)
	s_barrier
	s_setprio 1
	ds_read_b128 v[212:215], v96 offset:55296
	ds_read_b128 v[216:219], v210 offset:18432
	ds_read_b128 v[220:223], v210 offset:23040
	ds_read_b128 v[224:227], v96 offset:59904
	ds_read_b128 v[228:231], v96 offset:55328
	ds_read_b128 v[244:247], v210 offset:18464
	ds_read_b128 v[252:255], v210 offset:23072
	s_waitcnt lgkmcnt(5)
	v_mfma_f32_32x32x16_bf16 v[48:63], v[212:215], v[216:219], v[48:63]
	s_waitcnt lgkmcnt(4)
	v_mfma_f32_32x32x16_bf16 v[32:47], v[212:215], v[220:223], v[32:47]
	ds_read_b128 v[212:215], v96 offset:59936
	s_waitcnt lgkmcnt(4)
	v_mfma_f32_32x32x16_bf16 v[16:31], v[224:227], v[216:219], v[16:31]
	ds_read_b128 v[216:219], v96 offset:55360
	v_mfma_f32_32x32x16_bf16 v[0:15], v[224:227], v[220:223], v[0:15]
	ds_read_b128 v[224:227], v210 offset:18496
	ds_read_b128 v[220:223], v210 offset:23104
	s_waitcnt lgkmcnt(5)
	v_mfma_f32_32x32x16_bf16 v[48:63], v[228:231], v[244:247], v[48:63]
	s_waitcnt lgkmcnt(4)
	v_mfma_f32_32x32x16_bf16 v[32:47], v[228:231], v[252:255], v[32:47]
	ds_read_b128 v[228:231], v96 offset:59968
	s_waitcnt lgkmcnt(4)
	v_mfma_f32_32x32x16_bf16 v[16:31], v[212:215], v[244:247], v[16:31]
	ds_read_b128 v[244:247], v96 offset:55392
	v_mfma_f32_32x32x16_bf16 v[0:15], v[212:215], v[252:255], v[0:15]
	ds_read_b128 v[212:215], v210 offset:18528
	ds_read_b128 v[252:255], v210 offset:23136
	s_waitcnt lgkmcnt(5)
	v_mfma_f32_32x32x16_bf16 v[48:63], v[216:219], v[224:227], v[48:63]
	s_waitcnt vmcnt(15)
	ds_write_b128 v209, v[64:67]
	global_load_dwordx4 v[64:67], v[148:149], off offset:1280
	s_waitcnt lgkmcnt(5)
	v_mfma_f32_32x32x16_bf16 v[32:47], v[216:219], v[220:223], v[32:47]
	ds_read_b128 v[216:219], v96 offset:60000
	s_waitcnt vmcnt(15)
	ds_write_b128 v209, v[72:75] offset:4608
	global_load_dwordx4 v[72:75], v[150:151], off offset:1280
	s_waitcnt lgkmcnt(6)
	v_mfma_f32_32x32x16_bf16 v[16:31], v[228:231], v[224:227], v[16:31]
	s_waitcnt vmcnt(15)
	ds_write_b128 v209, v[76:79] offset:9216
	global_load_dwordx4 v[76:79], v[152:153], off offset:1280
	v_mfma_f32_32x32x16_bf16 v[0:15], v[228:231], v[220:223], v[0:15]
	s_waitcnt vmcnt(15)
	ds_write_b128 v209, v[80:83] offset:13824
	global_load_dwordx4 v[80:83], v[154:155], off offset:1280
	s_waitcnt lgkmcnt(6)
	v_mfma_f32_32x32x16_bf16 v[48:63], v[244:247], v[212:215], v[48:63]
	s_waitcnt vmcnt(15)
	ds_write_b128 v209, v[102:105] offset:36864
	global_load_dwordx4 v[102:105], v[146:147], off offset:1280
	s_waitcnt lgkmcnt(6)
	v_mfma_f32_32x32x16_bf16 v[32:47], v[244:247], v[252:255], v[32:47]
	s_waitcnt vmcnt(15)
	ds_write_b128 v209, v[118:121] offset:41472
	global_load_dwordx4 v[118:121], v[156:157], off offset:1280
	s_waitcnt lgkmcnt(5)
	v_mfma_f32_32x32x16_bf16 v[16:31], v[216:219], v[212:215], v[16:31]
	s_waitcnt vmcnt(15)
	ds_write_b128 v209, v[122:125] offset:46080
	global_load_dwordx4 v[122:125], v[158:159], off offset:1280
	v_mfma_f32_32x32x16_bf16 v[0:15], v[216:219], v[252:255], v[0:15]
	s_waitcnt vmcnt(15)
	ds_write_b128 v209, v[126:129] offset:50688
	global_load_dwordx4 v[126:129], v[160:161], off offset:1280
	s_setprio 0
	s_waitcnt lgkmcnt(0)
	s_barrier
	s_setprio 1
	ds_read_b128 v[212:215], v96 offset:36864
	ds_read_b128 v[216:219], v210
	ds_read_b128 v[220:223], v210 offset:4608
	ds_read_b128 v[224:227], v96 offset:41472
	ds_read_b128 v[228:231], v96 offset:36896
	ds_read_b128 v[244:247], v210 offset:32
	ds_read_b128 v[252:255], v210 offset:4640
	s_waitcnt lgkmcnt(5)
	v_mfma_f32_32x32x16_bf16 v[48:63], v[212:215], v[216:219], v[48:63]
	s_waitcnt lgkmcnt(4)
	v_mfma_f32_32x32x16_bf16 v[32:47], v[212:215], v[220:223], v[32:47]
	ds_read_b128 v[212:215], v96 offset:41504
	s_waitcnt lgkmcnt(4)
	v_mfma_f32_32x32x16_bf16 v[16:31], v[224:227], v[216:219], v[16:31]
	ds_read_b128 v[216:219], v96 offset:36928
	v_mfma_f32_32x32x16_bf16 v[0:15], v[224:227], v[220:223], v[0:15]
	ds_read_b128 v[224:227], v210 offset:64
	ds_read_b128 v[220:223], v210 offset:4672
	s_waitcnt lgkmcnt(5)
	v_mfma_f32_32x32x16_bf16 v[48:63], v[228:231], v[244:247], v[48:63]
	s_waitcnt lgkmcnt(4)
	v_mfma_f32_32x32x16_bf16 v[32:47], v[228:231], v[252:255], v[32:47]
	ds_read_b128 v[228:231], v96 offset:41536
	s_waitcnt lgkmcnt(4)
	v_mfma_f32_32x32x16_bf16 v[16:31], v[212:215], v[244:247], v[16:31]
	ds_read_b128 v[244:247], v96 offset:36960
	v_mfma_f32_32x32x16_bf16 v[0:15], v[212:215], v[252:255], v[0:15]
	ds_read_b128 v[212:215], v210 offset:96
	ds_read_b128 v[252:255], v210 offset:4704
	s_waitcnt lgkmcnt(5)
	v_mfma_f32_32x32x16_bf16 v[48:63], v[216:219], v[224:227], v[48:63]
	s_waitcnt vmcnt(15)
	ds_write_b128 v209, v[68:71] offset:18432
	global_load_dwordx4 v[68:71], v[148:149], off offset:1408
	s_waitcnt lgkmcnt(5)
	v_mfma_f32_32x32x16_bf16 v[32:47], v[216:219], v[220:223], v[32:47]
	ds_read_b128 v[216:219], v96 offset:41568
	s_waitcnt vmcnt(15)
	ds_write_b128 v209, v[84:87] offset:23040
	global_load_dwordx4 v[84:87], v[150:151], off offset:1408
	s_waitcnt lgkmcnt(6)
	v_mfma_f32_32x32x16_bf16 v[16:31], v[228:231], v[224:227], v[16:31]
	s_waitcnt vmcnt(15)
	ds_write_b128 v209, v[88:91] offset:27648
	global_load_dwordx4 v[88:91], v[152:153], off offset:1408
	v_mfma_f32_32x32x16_bf16 v[0:15], v[228:231], v[220:223], v[0:15]
	s_waitcnt vmcnt(15)
	ds_write_b128 v209, v[92:95] offset:32256
	global_load_dwordx4 v[92:95], v[154:155], off offset:1408
	s_waitcnt lgkmcnt(6)
	v_mfma_f32_32x32x16_bf16 v[48:63], v[244:247], v[212:215], v[48:63]
	s_waitcnt vmcnt(15)
	ds_write_b128 v209, v[98:101] offset:55296
	global_load_dwordx4 v[98:101], v[146:147], off offset:1408
	s_waitcnt lgkmcnt(6)
	v_mfma_f32_32x32x16_bf16 v[32:47], v[244:247], v[252:255], v[32:47]
	s_waitcnt vmcnt(15)
	ds_write_b128 v209, v[106:109] offset:59904
	global_load_dwordx4 v[106:109], v[156:157], off offset:1408
	s_waitcnt lgkmcnt(5)
	v_mfma_f32_32x32x16_bf16 v[16:31], v[216:219], v[212:215], v[16:31]
	s_waitcnt vmcnt(15)
	ds_write_b128 v209, v[110:113] offset:64512
	global_load_dwordx4 v[110:113], v[158:159], off offset:1408
	v_mfma_f32_32x32x16_bf16 v[0:15], v[216:219], v[252:255], v[0:15]
	s_waitcnt vmcnt(15)
	ds_write_b128 v211, v[114:117] offset:13824
	global_load_dwordx4 v[114:117], v[160:161], off offset:1408
	s_setprio 0
	s_waitcnt lgkmcnt(0)
	s_barrier
	s_setprio 1
	ds_read_b128 v[212:215], v96 offset:55296
	ds_read_b128 v[216:219], v210 offset:18432
	ds_read_b128 v[220:223], v210 offset:23040
	ds_read_b128 v[224:227], v96 offset:59904
	ds_read_b128 v[228:231], v96 offset:55328
	ds_read_b128 v[244:247], v210 offset:18464
	ds_read_b128 v[252:255], v210 offset:23072
	s_waitcnt lgkmcnt(5)
	v_mfma_f32_32x32x16_bf16 v[48:63], v[212:215], v[216:219], v[48:63]
	s_waitcnt lgkmcnt(4)
	v_mfma_f32_32x32x16_bf16 v[32:47], v[212:215], v[220:223], v[32:47]
	ds_read_b128 v[212:215], v96 offset:59936
	s_waitcnt lgkmcnt(4)
	v_mfma_f32_32x32x16_bf16 v[16:31], v[224:227], v[216:219], v[16:31]
	ds_read_b128 v[216:219], v96 offset:55360
	v_mfma_f32_32x32x16_bf16 v[0:15], v[224:227], v[220:223], v[0:15]
	ds_read_b128 v[224:227], v210 offset:18496
	ds_read_b128 v[220:223], v210 offset:23104
	s_waitcnt lgkmcnt(5)
	v_mfma_f32_32x32x16_bf16 v[48:63], v[228:231], v[244:247], v[48:63]
	s_waitcnt lgkmcnt(4)
	v_mfma_f32_32x32x16_bf16 v[32:47], v[228:231], v[252:255], v[32:47]
	ds_read_b128 v[228:231], v96 offset:59968
	s_waitcnt lgkmcnt(4)
	v_mfma_f32_32x32x16_bf16 v[16:31], v[212:215], v[244:247], v[16:31]
	ds_read_b128 v[244:247], v96 offset:55392
	v_mfma_f32_32x32x16_bf16 v[0:15], v[212:215], v[252:255], v[0:15]
	ds_read_b128 v[212:215], v210 offset:18528
	ds_read_b128 v[252:255], v210 offset:23136
	s_waitcnt lgkmcnt(5)
	v_mfma_f32_32x32x16_bf16 v[48:63], v[216:219], v[224:227], v[48:63]
	s_waitcnt vmcnt(15)
	ds_write_b128 v209, v[64:67]
	global_load_dwordx4 v[64:67], v[148:149], off offset:1536
	s_waitcnt lgkmcnt(5)
	v_mfma_f32_32x32x16_bf16 v[32:47], v[216:219], v[220:223], v[32:47]
	ds_read_b128 v[216:219], v96 offset:60000
	s_waitcnt vmcnt(15)
	ds_write_b128 v209, v[72:75] offset:4608
	global_load_dwordx4 v[72:75], v[150:151], off offset:1536
	s_waitcnt lgkmcnt(6)
	v_mfma_f32_32x32x16_bf16 v[16:31], v[228:231], v[224:227], v[16:31]
	s_waitcnt vmcnt(15)
	ds_write_b128 v209, v[76:79] offset:9216
	global_load_dwordx4 v[76:79], v[152:153], off offset:1536
	v_mfma_f32_32x32x16_bf16 v[0:15], v[228:231], v[220:223], v[0:15]
	s_waitcnt vmcnt(15)
	ds_write_b128 v209, v[80:83] offset:13824
	global_load_dwordx4 v[80:83], v[154:155], off offset:1536
	s_waitcnt lgkmcnt(6)
	v_mfma_f32_32x32x16_bf16 v[48:63], v[244:247], v[212:215], v[48:63]
	s_waitcnt vmcnt(15)
	ds_write_b128 v209, v[102:105] offset:36864
	global_load_dwordx4 v[102:105], v[146:147], off offset:1536
	s_waitcnt lgkmcnt(6)
	v_mfma_f32_32x32x16_bf16 v[32:47], v[244:247], v[252:255], v[32:47]
	s_waitcnt vmcnt(15)
	ds_write_b128 v209, v[118:121] offset:41472
	global_load_dwordx4 v[118:121], v[156:157], off offset:1536
	s_waitcnt lgkmcnt(5)
	v_mfma_f32_32x32x16_bf16 v[16:31], v[216:219], v[212:215], v[16:31]
	s_waitcnt vmcnt(15)
	ds_write_b128 v209, v[122:125] offset:46080
	global_load_dwordx4 v[122:125], v[158:159], off offset:1536
	v_mfma_f32_32x32x16_bf16 v[0:15], v[216:219], v[252:255], v[0:15]
	s_waitcnt vmcnt(15)
	ds_write_b128 v209, v[126:129] offset:50688
	global_load_dwordx4 v[126:129], v[160:161], off offset:1536
	s_setprio 0
	s_waitcnt lgkmcnt(0)
	s_barrier
	s_setprio 1
	ds_read_b128 v[212:215], v96 offset:36864
	ds_read_b128 v[216:219], v210
	ds_read_b128 v[220:223], v210 offset:4608
	ds_read_b128 v[224:227], v96 offset:41472
	ds_read_b128 v[228:231], v96 offset:36896
	ds_read_b128 v[244:247], v210 offset:32
	ds_read_b128 v[252:255], v210 offset:4640
	s_waitcnt lgkmcnt(5)
	v_mfma_f32_32x32x16_bf16 v[48:63], v[212:215], v[216:219], v[48:63]
	s_waitcnt lgkmcnt(4)
	v_mfma_f32_32x32x16_bf16 v[32:47], v[212:215], v[220:223], v[32:47]
	ds_read_b128 v[212:215], v96 offset:41504
	s_waitcnt lgkmcnt(4)
	v_mfma_f32_32x32x16_bf16 v[16:31], v[224:227], v[216:219], v[16:31]
	ds_read_b128 v[216:219], v96 offset:36928
	v_mfma_f32_32x32x16_bf16 v[0:15], v[224:227], v[220:223], v[0:15]
	ds_read_b128 v[224:227], v210 offset:64
	ds_read_b128 v[220:223], v210 offset:4672
	s_waitcnt lgkmcnt(5)
	v_mfma_f32_32x32x16_bf16 v[48:63], v[228:231], v[244:247], v[48:63]
	s_waitcnt lgkmcnt(4)
	v_mfma_f32_32x32x16_bf16 v[32:47], v[228:231], v[252:255], v[32:47]
	ds_read_b128 v[228:231], v96 offset:41536
	s_waitcnt lgkmcnt(4)
	v_mfma_f32_32x32x16_bf16 v[16:31], v[212:215], v[244:247], v[16:31]
	ds_read_b128 v[244:247], v96 offset:36960
	v_mfma_f32_32x32x16_bf16 v[0:15], v[212:215], v[252:255], v[0:15]
	ds_read_b128 v[212:215], v210 offset:96
	ds_read_b128 v[252:255], v210 offset:4704
	s_waitcnt lgkmcnt(5)
	v_mfma_f32_32x32x16_bf16 v[48:63], v[216:219], v[224:227], v[48:63]
	s_waitcnt vmcnt(15)
	ds_write_b128 v209, v[68:71] offset:18432
	global_load_dwordx4 v[68:71], v[148:149], off offset:1664
	s_waitcnt lgkmcnt(5)
	v_mfma_f32_32x32x16_bf16 v[32:47], v[216:219], v[220:223], v[32:47]
	ds_read_b128 v[216:219], v96 offset:41568
	s_waitcnt vmcnt(15)
	ds_write_b128 v209, v[84:87] offset:23040
	global_load_dwordx4 v[84:87], v[150:151], off offset:1664
	s_waitcnt lgkmcnt(6)
	v_mfma_f32_32x32x16_bf16 v[16:31], v[228:231], v[224:227], v[16:31]
	s_waitcnt vmcnt(15)
	ds_write_b128 v209, v[88:91] offset:27648
	global_load_dwordx4 v[88:91], v[152:153], off offset:1664
	v_mfma_f32_32x32x16_bf16 v[0:15], v[228:231], v[220:223], v[0:15]
	s_waitcnt vmcnt(15)
	ds_write_b128 v209, v[92:95] offset:32256
	global_load_dwordx4 v[92:95], v[154:155], off offset:1664
	s_waitcnt lgkmcnt(6)
	v_mfma_f32_32x32x16_bf16 v[48:63], v[244:247], v[212:215], v[48:63]
	s_waitcnt vmcnt(15)
	ds_write_b128 v209, v[98:101] offset:55296
	global_load_dwordx4 v[98:101], v[146:147], off offset:1664
	s_waitcnt lgkmcnt(6)
	v_mfma_f32_32x32x16_bf16 v[32:47], v[244:247], v[252:255], v[32:47]
	s_waitcnt vmcnt(15)
	ds_write_b128 v209, v[106:109] offset:59904
	global_load_dwordx4 v[106:109], v[156:157], off offset:1664
	s_waitcnt lgkmcnt(5)
	v_mfma_f32_32x32x16_bf16 v[16:31], v[216:219], v[212:215], v[16:31]
	s_waitcnt vmcnt(15)
	ds_write_b128 v209, v[110:113] offset:64512
	global_load_dwordx4 v[110:113], v[158:159], off offset:1664
	v_mfma_f32_32x32x16_bf16 v[0:15], v[216:219], v[252:255], v[0:15]
	s_waitcnt vmcnt(15)
	ds_write_b128 v211, v[114:117] offset:13824
	global_load_dwordx4 v[114:117], v[160:161], off offset:1664
	s_setprio 0
	s_waitcnt lgkmcnt(0)
	s_barrier
	s_setprio 1
	ds_read_b128 v[212:215], v96 offset:55296
	ds_read_b128 v[216:219], v210 offset:18432
	ds_read_b128 v[220:223], v210 offset:23040
	ds_read_b128 v[224:227], v96 offset:59904
	ds_read_b128 v[228:231], v96 offset:55328
	ds_read_b128 v[244:247], v210 offset:18464
	ds_read_b128 v[252:255], v210 offset:23072
	s_waitcnt lgkmcnt(5)
	v_mfma_f32_32x32x16_bf16 v[48:63], v[212:215], v[216:219], v[48:63]
	s_waitcnt lgkmcnt(4)
	v_mfma_f32_32x32x16_bf16 v[32:47], v[212:215], v[220:223], v[32:47]
	ds_read_b128 v[212:215], v96 offset:59936
	s_waitcnt lgkmcnt(4)
	v_mfma_f32_32x32x16_bf16 v[16:31], v[224:227], v[216:219], v[16:31]
	ds_read_b128 v[216:219], v96 offset:55360
	v_mfma_f32_32x32x16_bf16 v[0:15], v[224:227], v[220:223], v[0:15]
	ds_read_b128 v[224:227], v210 offset:18496
	ds_read_b128 v[220:223], v210 offset:23104
	s_waitcnt lgkmcnt(5)
	v_mfma_f32_32x32x16_bf16 v[48:63], v[228:231], v[244:247], v[48:63]
	s_waitcnt lgkmcnt(4)
	v_mfma_f32_32x32x16_bf16 v[32:47], v[228:231], v[252:255], v[32:47]
	ds_read_b128 v[228:231], v96 offset:59968
	s_waitcnt lgkmcnt(4)
	v_mfma_f32_32x32x16_bf16 v[16:31], v[212:215], v[244:247], v[16:31]
	ds_read_b128 v[244:247], v96 offset:55392
	v_mfma_f32_32x32x16_bf16 v[0:15], v[212:215], v[252:255], v[0:15]
	ds_read_b128 v[212:215], v210 offset:18528
	ds_read_b128 v[252:255], v210 offset:23136
	s_waitcnt lgkmcnt(5)
	v_mfma_f32_32x32x16_bf16 v[48:63], v[216:219], v[224:227], v[48:63]
	s_waitcnt vmcnt(15)
	ds_write_b128 v209, v[64:67]
	global_load_dwordx4 v[64:67], v[148:149], off offset:1792
	s_waitcnt lgkmcnt(5)
	v_mfma_f32_32x32x16_bf16 v[32:47], v[216:219], v[220:223], v[32:47]
	ds_read_b128 v[216:219], v96 offset:60000
	s_waitcnt vmcnt(15)
	ds_write_b128 v209, v[72:75] offset:4608
	global_load_dwordx4 v[72:75], v[150:151], off offset:1792
	s_waitcnt lgkmcnt(6)
	v_mfma_f32_32x32x16_bf16 v[16:31], v[228:231], v[224:227], v[16:31]
	s_waitcnt vmcnt(15)
	ds_write_b128 v209, v[76:79] offset:9216
	global_load_dwordx4 v[76:79], v[152:153], off offset:1792
	v_mfma_f32_32x32x16_bf16 v[0:15], v[228:231], v[220:223], v[0:15]
	s_waitcnt vmcnt(15)
	ds_write_b128 v209, v[80:83] offset:13824
	global_load_dwordx4 v[80:83], v[154:155], off offset:1792
	s_waitcnt lgkmcnt(6)
	v_mfma_f32_32x32x16_bf16 v[48:63], v[244:247], v[212:215], v[48:63]
	s_waitcnt vmcnt(15)
	ds_write_b128 v209, v[102:105] offset:36864
	global_load_dwordx4 v[102:105], v[146:147], off offset:1792
	s_waitcnt lgkmcnt(6)
	v_mfma_f32_32x32x16_bf16 v[32:47], v[244:247], v[252:255], v[32:47]
	s_waitcnt vmcnt(15)
	ds_write_b128 v209, v[118:121] offset:41472
	global_load_dwordx4 v[118:121], v[156:157], off offset:1792
	s_waitcnt lgkmcnt(5)
	v_mfma_f32_32x32x16_bf16 v[16:31], v[216:219], v[212:215], v[16:31]
	s_waitcnt vmcnt(15)
	ds_write_b128 v209, v[122:125] offset:46080
	global_load_dwordx4 v[122:125], v[158:159], off offset:1792
	v_mfma_f32_32x32x16_bf16 v[0:15], v[216:219], v[252:255], v[0:15]
	s_waitcnt vmcnt(15)
	ds_write_b128 v209, v[126:129] offset:50688
	global_load_dwordx4 v[126:129], v[160:161], off offset:1792
	s_setprio 0
	s_waitcnt lgkmcnt(0)
	s_barrier
	s_setprio 1
	ds_read_b128 v[212:215], v96 offset:36864
	ds_read_b128 v[216:219], v210
	ds_read_b128 v[220:223], v210 offset:4608
	ds_read_b128 v[224:227], v96 offset:41472
	ds_read_b128 v[228:231], v96 offset:36896
	ds_read_b128 v[244:247], v210 offset:32
	ds_read_b128 v[252:255], v210 offset:4640
	s_waitcnt lgkmcnt(5)
	v_mfma_f32_32x32x16_bf16 v[48:63], v[212:215], v[216:219], v[48:63]
	s_waitcnt lgkmcnt(4)
	v_mfma_f32_32x32x16_bf16 v[32:47], v[212:215], v[220:223], v[32:47]
	ds_read_b128 v[212:215], v96 offset:41504
	s_waitcnt lgkmcnt(4)
	v_mfma_f32_32x32x16_bf16 v[16:31], v[224:227], v[216:219], v[16:31]
	ds_read_b128 v[216:219], v96 offset:36928
	v_mfma_f32_32x32x16_bf16 v[0:15], v[224:227], v[220:223], v[0:15]
	ds_read_b128 v[224:227], v210 offset:64
	ds_read_b128 v[220:223], v210 offset:4672
	s_waitcnt lgkmcnt(5)
	v_mfma_f32_32x32x16_bf16 v[48:63], v[228:231], v[244:247], v[48:63]
	s_waitcnt lgkmcnt(4)
	v_mfma_f32_32x32x16_bf16 v[32:47], v[228:231], v[252:255], v[32:47]
	ds_read_b128 v[228:231], v96 offset:41536
	s_waitcnt lgkmcnt(4)
	v_mfma_f32_32x32x16_bf16 v[16:31], v[212:215], v[244:247], v[16:31]
	ds_read_b128 v[244:247], v96 offset:36960
	v_mfma_f32_32x32x16_bf16 v[0:15], v[212:215], v[252:255], v[0:15]
	ds_read_b128 v[212:215], v210 offset:96
	ds_read_b128 v[252:255], v210 offset:4704
	s_waitcnt lgkmcnt(5)
	v_mfma_f32_32x32x16_bf16 v[48:63], v[216:219], v[224:227], v[48:63]
	s_waitcnt vmcnt(15)
	ds_write_b128 v209, v[68:71] offset:18432
	global_load_dwordx4 v[68:71], v[148:149], off offset:1920
	s_waitcnt lgkmcnt(5)
	v_mfma_f32_32x32x16_bf16 v[32:47], v[216:219], v[220:223], v[32:47]
	ds_read_b128 v[216:219], v96 offset:41568
	s_waitcnt vmcnt(15)
	ds_write_b128 v209, v[84:87] offset:23040
	global_load_dwordx4 v[84:87], v[150:151], off offset:1920
	s_waitcnt lgkmcnt(6)
	v_mfma_f32_32x32x16_bf16 v[16:31], v[228:231], v[224:227], v[16:31]
	s_waitcnt vmcnt(15)
	ds_write_b128 v209, v[88:91] offset:27648
	global_load_dwordx4 v[88:91], v[152:153], off offset:1920
	v_mfma_f32_32x32x16_bf16 v[0:15], v[228:231], v[220:223], v[0:15]
	s_waitcnt vmcnt(15)
	ds_write_b128 v209, v[92:95] offset:32256
	global_load_dwordx4 v[92:95], v[154:155], off offset:1920
	s_waitcnt lgkmcnt(6)
	v_mfma_f32_32x32x16_bf16 v[48:63], v[244:247], v[212:215], v[48:63]
	s_waitcnt vmcnt(15)
	ds_write_b128 v209, v[98:101] offset:55296
	global_load_dwordx4 v[98:101], v[146:147], off offset:1920
	s_waitcnt lgkmcnt(6)
	v_mfma_f32_32x32x16_bf16 v[32:47], v[244:247], v[252:255], v[32:47]
	s_waitcnt vmcnt(15)
	ds_write_b128 v209, v[106:109] offset:59904
	global_load_dwordx4 v[106:109], v[156:157], off offset:1920
	s_waitcnt lgkmcnt(5)
	v_mfma_f32_32x32x16_bf16 v[16:31], v[216:219], v[212:215], v[16:31]
	s_waitcnt vmcnt(15)
	ds_write_b128 v209, v[110:113] offset:64512
	global_load_dwordx4 v[110:113], v[158:159], off offset:1920
	v_mfma_f32_32x32x16_bf16 v[0:15], v[216:219], v[252:255], v[0:15]
	s_waitcnt vmcnt(15)
	ds_write_b128 v211, v[114:117] offset:13824
	global_load_dwordx4 v[114:117], v[160:161], off offset:1920
	s_setprio 0
	s_waitcnt lgkmcnt(0)
	s_barrier
	s_setprio 1
	ds_read_b128 v[212:215], v96 offset:55296
	ds_read_b128 v[216:219], v210 offset:18432
	ds_read_b128 v[220:223], v210 offset:23040
	ds_read_b128 v[224:227], v96 offset:59904
	ds_read_b128 v[228:231], v96 offset:55328
	ds_read_b128 v[244:247], v210 offset:18464
	ds_read_b128 v[252:255], v210 offset:23072
	s_waitcnt lgkmcnt(5)
	v_mfma_f32_32x32x16_bf16 v[48:63], v[212:215], v[216:219], v[48:63]
	s_waitcnt lgkmcnt(4)
	v_mfma_f32_32x32x16_bf16 v[32:47], v[212:215], v[220:223], v[32:47]
	ds_read_b128 v[212:215], v96 offset:59936
	s_waitcnt lgkmcnt(4)
	v_mfma_f32_32x32x16_bf16 v[16:31], v[224:227], v[216:219], v[16:31]
	ds_read_b128 v[216:219], v96 offset:55360
	v_mfma_f32_32x32x16_bf16 v[0:15], v[224:227], v[220:223], v[0:15]
	ds_read_b128 v[224:227], v210 offset:18496
	ds_read_b128 v[220:223], v210 offset:23104
	s_waitcnt lgkmcnt(5)
	v_mfma_f32_32x32x16_bf16 v[48:63], v[228:231], v[244:247], v[48:63]
	s_waitcnt lgkmcnt(4)
	v_mfma_f32_32x32x16_bf16 v[32:47], v[228:231], v[252:255], v[32:47]
	ds_read_b128 v[228:231], v96 offset:59968
	s_waitcnt lgkmcnt(4)
	v_mfma_f32_32x32x16_bf16 v[16:31], v[212:215], v[244:247], v[16:31]
	ds_read_b128 v[244:247], v96 offset:55392
	v_mfma_f32_32x32x16_bf16 v[0:15], v[212:215], v[252:255], v[0:15]
	ds_read_b128 v[212:215], v210 offset:18528
	ds_read_b128 v[252:255], v210 offset:23136
	s_waitcnt lgkmcnt(5)
	v_mfma_f32_32x32x16_bf16 v[48:63], v[216:219], v[224:227], v[48:63]
	s_waitcnt vmcnt(15)
	ds_write_b128 v209, v[64:67]
	global_load_dwordx4 v[64:67], v[148:149], off offset:2048
	s_waitcnt lgkmcnt(5)
	v_mfma_f32_32x32x16_bf16 v[32:47], v[216:219], v[220:223], v[32:47]
	ds_read_b128 v[216:219], v96 offset:60000
	s_waitcnt vmcnt(15)
	ds_write_b128 v209, v[72:75] offset:4608
	global_load_dwordx4 v[72:75], v[150:151], off offset:2048
	s_waitcnt lgkmcnt(6)
	v_mfma_f32_32x32x16_bf16 v[16:31], v[228:231], v[224:227], v[16:31]
	s_waitcnt vmcnt(15)
	ds_write_b128 v209, v[76:79] offset:9216
	global_load_dwordx4 v[76:79], v[152:153], off offset:2048
	v_mfma_f32_32x32x16_bf16 v[0:15], v[228:231], v[220:223], v[0:15]
	s_waitcnt vmcnt(15)
	ds_write_b128 v209, v[80:83] offset:13824
	global_load_dwordx4 v[80:83], v[154:155], off offset:2048
	s_waitcnt lgkmcnt(6)
	v_mfma_f32_32x32x16_bf16 v[48:63], v[244:247], v[212:215], v[48:63]
	s_waitcnt vmcnt(15)
	ds_write_b128 v209, v[102:105] offset:36864
	global_load_dwordx4 v[102:105], v[146:147], off offset:2048
	s_waitcnt lgkmcnt(6)
	v_mfma_f32_32x32x16_bf16 v[32:47], v[244:247], v[252:255], v[32:47]
	s_waitcnt vmcnt(15)
	ds_write_b128 v209, v[118:121] offset:41472
	global_load_dwordx4 v[118:121], v[156:157], off offset:2048
	s_waitcnt lgkmcnt(5)
	v_mfma_f32_32x32x16_bf16 v[16:31], v[216:219], v[212:215], v[16:31]
	s_waitcnt vmcnt(15)
	ds_write_b128 v209, v[122:125] offset:46080
	global_load_dwordx4 v[122:125], v[158:159], off offset:2048
	v_mfma_f32_32x32x16_bf16 v[0:15], v[216:219], v[252:255], v[0:15]
	s_waitcnt vmcnt(15)
	ds_write_b128 v209, v[126:129] offset:50688
	global_load_dwordx4 v[126:129], v[160:161], off offset:2048
	s_setprio 0
	s_waitcnt lgkmcnt(0)
	s_barrier
	s_setprio 1
	ds_read_b128 v[212:215], v96 offset:36864
	ds_read_b128 v[216:219], v210
	ds_read_b128 v[220:223], v210 offset:4608
	ds_read_b128 v[224:227], v96 offset:41472
	ds_read_b128 v[228:231], v96 offset:36896
	ds_read_b128 v[244:247], v210 offset:32
	ds_read_b128 v[252:255], v210 offset:4640
	s_waitcnt lgkmcnt(5)
	v_mfma_f32_32x32x16_bf16 v[48:63], v[212:215], v[216:219], v[48:63]
	s_waitcnt lgkmcnt(4)
	v_mfma_f32_32x32x16_bf16 v[32:47], v[212:215], v[220:223], v[32:47]
	ds_read_b128 v[212:215], v96 offset:41504
	s_waitcnt lgkmcnt(4)
	v_mfma_f32_32x32x16_bf16 v[16:31], v[224:227], v[216:219], v[16:31]
	ds_read_b128 v[216:219], v96 offset:36928
	v_mfma_f32_32x32x16_bf16 v[0:15], v[224:227], v[220:223], v[0:15]
	ds_read_b128 v[224:227], v210 offset:64
	ds_read_b128 v[220:223], v210 offset:4672
	s_waitcnt lgkmcnt(5)
	v_mfma_f32_32x32x16_bf16 v[48:63], v[228:231], v[244:247], v[48:63]
	s_waitcnt lgkmcnt(4)
	v_mfma_f32_32x32x16_bf16 v[32:47], v[228:231], v[252:255], v[32:47]
	ds_read_b128 v[228:231], v96 offset:41536
	s_waitcnt lgkmcnt(4)
	v_mfma_f32_32x32x16_bf16 v[16:31], v[212:215], v[244:247], v[16:31]
	ds_read_b128 v[244:247], v96 offset:36960
	v_mfma_f32_32x32x16_bf16 v[0:15], v[212:215], v[252:255], v[0:15]
	ds_read_b128 v[212:215], v210 offset:96
	ds_read_b128 v[252:255], v210 offset:4704
	s_waitcnt lgkmcnt(5)
	v_mfma_f32_32x32x16_bf16 v[48:63], v[216:219], v[224:227], v[48:63]
	s_waitcnt vmcnt(15)
	ds_write_b128 v209, v[68:71] offset:18432
	global_load_dwordx4 v[68:71], v[148:149], off offset:2176
	s_waitcnt lgkmcnt(5)
	v_mfma_f32_32x32x16_bf16 v[32:47], v[216:219], v[220:223], v[32:47]
	ds_read_b128 v[216:219], v96 offset:41568
	s_waitcnt vmcnt(15)
	ds_write_b128 v209, v[84:87] offset:23040
	global_load_dwordx4 v[84:87], v[150:151], off offset:2176
	s_waitcnt lgkmcnt(6)
	v_mfma_f32_32x32x16_bf16 v[16:31], v[228:231], v[224:227], v[16:31]
	s_waitcnt vmcnt(15)
	ds_write_b128 v209, v[88:91] offset:27648
	global_load_dwordx4 v[88:91], v[152:153], off offset:2176
	v_mfma_f32_32x32x16_bf16 v[0:15], v[228:231], v[220:223], v[0:15]
	s_waitcnt vmcnt(15)
	ds_write_b128 v209, v[92:95] offset:32256
	global_load_dwordx4 v[92:95], v[154:155], off offset:2176
	s_waitcnt lgkmcnt(6)
	v_mfma_f32_32x32x16_bf16 v[48:63], v[244:247], v[212:215], v[48:63]
	s_waitcnt vmcnt(15)
	ds_write_b128 v209, v[98:101] offset:55296
	global_load_dwordx4 v[98:101], v[146:147], off offset:2176
	s_waitcnt lgkmcnt(6)
	v_mfma_f32_32x32x16_bf16 v[32:47], v[244:247], v[252:255], v[32:47]
	s_waitcnt vmcnt(15)
	ds_write_b128 v209, v[106:109] offset:59904
	global_load_dwordx4 v[106:109], v[156:157], off offset:2176
	s_waitcnt lgkmcnt(5)
	v_mfma_f32_32x32x16_bf16 v[16:31], v[216:219], v[212:215], v[16:31]
	s_waitcnt vmcnt(15)
	ds_write_b128 v209, v[110:113] offset:64512
	global_load_dwordx4 v[110:113], v[158:159], off offset:2176
	v_mfma_f32_32x32x16_bf16 v[0:15], v[216:219], v[252:255], v[0:15]
	s_waitcnt vmcnt(15)
	ds_write_b128 v211, v[114:117] offset:13824
	global_load_dwordx4 v[114:117], v[160:161], off offset:2176
	s_setprio 0
	s_waitcnt lgkmcnt(0)
	s_barrier
	s_setprio 1
	ds_read_b128 v[212:215], v96 offset:55296
	ds_read_b128 v[216:219], v210 offset:18432
	ds_read_b128 v[220:223], v210 offset:23040
	ds_read_b128 v[224:227], v96 offset:59904
	ds_read_b128 v[228:231], v96 offset:55328
	ds_read_b128 v[244:247], v210 offset:18464
	ds_read_b128 v[252:255], v210 offset:23072
	s_waitcnt lgkmcnt(5)
	v_mfma_f32_32x32x16_bf16 v[48:63], v[212:215], v[216:219], v[48:63]
	s_waitcnt lgkmcnt(4)
	v_mfma_f32_32x32x16_bf16 v[32:47], v[212:215], v[220:223], v[32:47]
	ds_read_b128 v[212:215], v96 offset:59936
	s_waitcnt lgkmcnt(4)
	v_mfma_f32_32x32x16_bf16 v[16:31], v[224:227], v[216:219], v[16:31]
	ds_read_b128 v[216:219], v96 offset:55360
	v_mfma_f32_32x32x16_bf16 v[0:15], v[224:227], v[220:223], v[0:15]
	ds_read_b128 v[224:227], v210 offset:18496
	ds_read_b128 v[220:223], v210 offset:23104
	s_waitcnt lgkmcnt(5)
	v_mfma_f32_32x32x16_bf16 v[48:63], v[228:231], v[244:247], v[48:63]
	s_waitcnt lgkmcnt(4)
	v_mfma_f32_32x32x16_bf16 v[32:47], v[228:231], v[252:255], v[32:47]
	ds_read_b128 v[228:231], v96 offset:59968
	s_waitcnt lgkmcnt(4)
	v_mfma_f32_32x32x16_bf16 v[16:31], v[212:215], v[244:247], v[16:31]
	ds_read_b128 v[244:247], v96 offset:55392
	v_mfma_f32_32x32x16_bf16 v[0:15], v[212:215], v[252:255], v[0:15]
	ds_read_b128 v[212:215], v210 offset:18528
	ds_read_b128 v[252:255], v210 offset:23136
	s_waitcnt lgkmcnt(5)
	v_mfma_f32_32x32x16_bf16 v[48:63], v[216:219], v[224:227], v[48:63]
	s_waitcnt vmcnt(15)
	ds_write_b128 v209, v[64:67]
	global_load_dwordx4 v[64:67], v[148:149], off offset:2304
	s_waitcnt lgkmcnt(5)
	v_mfma_f32_32x32x16_bf16 v[32:47], v[216:219], v[220:223], v[32:47]
	ds_read_b128 v[216:219], v96 offset:60000
	s_waitcnt vmcnt(15)
	ds_write_b128 v209, v[72:75] offset:4608
	global_load_dwordx4 v[72:75], v[150:151], off offset:2304
	s_waitcnt lgkmcnt(6)
	v_mfma_f32_32x32x16_bf16 v[16:31], v[228:231], v[224:227], v[16:31]
	s_waitcnt vmcnt(15)
	ds_write_b128 v209, v[76:79] offset:9216
	global_load_dwordx4 v[76:79], v[152:153], off offset:2304
	v_mfma_f32_32x32x16_bf16 v[0:15], v[228:231], v[220:223], v[0:15]
	s_waitcnt vmcnt(15)
	ds_write_b128 v209, v[80:83] offset:13824
	global_load_dwordx4 v[80:83], v[154:155], off offset:2304
	s_waitcnt lgkmcnt(6)
	v_mfma_f32_32x32x16_bf16 v[48:63], v[244:247], v[212:215], v[48:63]
	s_waitcnt vmcnt(15)
	ds_write_b128 v209, v[102:105] offset:36864
	global_load_dwordx4 v[102:105], v[146:147], off offset:2304
	s_waitcnt lgkmcnt(6)
	v_mfma_f32_32x32x16_bf16 v[32:47], v[244:247], v[252:255], v[32:47]
	s_waitcnt vmcnt(15)
	ds_write_b128 v209, v[118:121] offset:41472
	global_load_dwordx4 v[118:121], v[156:157], off offset:2304
	s_waitcnt lgkmcnt(5)
	v_mfma_f32_32x32x16_bf16 v[16:31], v[216:219], v[212:215], v[16:31]
	s_waitcnt vmcnt(15)
	ds_write_b128 v209, v[122:125] offset:46080
	global_load_dwordx4 v[122:125], v[158:159], off offset:2304
	v_mfma_f32_32x32x16_bf16 v[0:15], v[216:219], v[252:255], v[0:15]
	s_waitcnt vmcnt(15)
	ds_write_b128 v209, v[126:129] offset:50688
	global_load_dwordx4 v[126:129], v[160:161], off offset:2304
	s_setprio 0
	s_waitcnt lgkmcnt(0)
	s_barrier
	s_setprio 1
	ds_read_b128 v[212:215], v96 offset:36864
	ds_read_b128 v[216:219], v210
	ds_read_b128 v[220:223], v210 offset:4608
	ds_read_b128 v[224:227], v96 offset:41472
	ds_read_b128 v[228:231], v96 offset:36896
	ds_read_b128 v[244:247], v210 offset:32
	ds_read_b128 v[252:255], v210 offset:4640
	s_waitcnt lgkmcnt(5)
	v_mfma_f32_32x32x16_bf16 v[48:63], v[212:215], v[216:219], v[48:63]
	s_waitcnt lgkmcnt(4)
	v_mfma_f32_32x32x16_bf16 v[32:47], v[212:215], v[220:223], v[32:47]
	ds_read_b128 v[212:215], v96 offset:41504
	s_waitcnt lgkmcnt(4)
	v_mfma_f32_32x32x16_bf16 v[16:31], v[224:227], v[216:219], v[16:31]
	ds_read_b128 v[216:219], v96 offset:36928
	v_mfma_f32_32x32x16_bf16 v[0:15], v[224:227], v[220:223], v[0:15]
	ds_read_b128 v[224:227], v210 offset:64
	ds_read_b128 v[220:223], v210 offset:4672
	s_waitcnt lgkmcnt(5)
	v_mfma_f32_32x32x16_bf16 v[48:63], v[228:231], v[244:247], v[48:63]
	s_waitcnt lgkmcnt(4)
	v_mfma_f32_32x32x16_bf16 v[32:47], v[228:231], v[252:255], v[32:47]
	ds_read_b128 v[228:231], v96 offset:41536
	s_waitcnt lgkmcnt(4)
	v_mfma_f32_32x32x16_bf16 v[16:31], v[212:215], v[244:247], v[16:31]
	ds_read_b128 v[244:247], v96 offset:36960
	v_mfma_f32_32x32x16_bf16 v[0:15], v[212:215], v[252:255], v[0:15]
	ds_read_b128 v[212:215], v210 offset:96
	ds_read_b128 v[252:255], v210 offset:4704
	s_waitcnt lgkmcnt(5)
	v_mfma_f32_32x32x16_bf16 v[48:63], v[216:219], v[224:227], v[48:63]
	s_waitcnt vmcnt(15)
	ds_write_b128 v209, v[68:71] offset:18432
	global_load_dwordx4 v[68:71], v[148:149], off offset:2432
	s_waitcnt lgkmcnt(5)
	v_mfma_f32_32x32x16_bf16 v[32:47], v[216:219], v[220:223], v[32:47]
	ds_read_b128 v[216:219], v96 offset:41568
	s_waitcnt vmcnt(15)
	ds_write_b128 v209, v[84:87] offset:23040
	global_load_dwordx4 v[84:87], v[150:151], off offset:2432
	s_waitcnt lgkmcnt(6)
	v_mfma_f32_32x32x16_bf16 v[16:31], v[228:231], v[224:227], v[16:31]
	s_waitcnt vmcnt(15)
	ds_write_b128 v209, v[88:91] offset:27648
	global_load_dwordx4 v[88:91], v[152:153], off offset:2432
	v_mfma_f32_32x32x16_bf16 v[0:15], v[228:231], v[220:223], v[0:15]
	s_waitcnt vmcnt(15)
	ds_write_b128 v209, v[92:95] offset:32256
	global_load_dwordx4 v[92:95], v[154:155], off offset:2432
	s_waitcnt lgkmcnt(6)
	v_mfma_f32_32x32x16_bf16 v[48:63], v[244:247], v[212:215], v[48:63]
	s_waitcnt vmcnt(15)
	ds_write_b128 v209, v[98:101] offset:55296
	global_load_dwordx4 v[98:101], v[146:147], off offset:2432
	s_waitcnt lgkmcnt(6)
	v_mfma_f32_32x32x16_bf16 v[32:47], v[244:247], v[252:255], v[32:47]
	s_waitcnt vmcnt(15)
	ds_write_b128 v209, v[106:109] offset:59904
	global_load_dwordx4 v[106:109], v[156:157], off offset:2432
	s_waitcnt lgkmcnt(5)
	v_mfma_f32_32x32x16_bf16 v[16:31], v[216:219], v[212:215], v[16:31]
	s_waitcnt vmcnt(15)
	ds_write_b128 v209, v[110:113] offset:64512
	global_load_dwordx4 v[110:113], v[158:159], off offset:2432
	v_mfma_f32_32x32x16_bf16 v[0:15], v[216:219], v[252:255], v[0:15]
	s_waitcnt vmcnt(15)
	ds_write_b128 v211, v[114:117] offset:13824
	global_load_dwordx4 v[114:117], v[160:161], off offset:2432
	s_setprio 0
	s_waitcnt lgkmcnt(0)
	s_barrier
	s_setprio 1
	ds_read_b128 v[212:215], v96 offset:55296
	ds_read_b128 v[216:219], v210 offset:18432
	ds_read_b128 v[220:223], v210 offset:23040
	ds_read_b128 v[224:227], v96 offset:59904
	ds_read_b128 v[228:231], v96 offset:55328
	ds_read_b128 v[244:247], v210 offset:18464
	ds_read_b128 v[252:255], v210 offset:23072
	s_waitcnt lgkmcnt(5)
	v_mfma_f32_32x32x16_bf16 v[48:63], v[212:215], v[216:219], v[48:63]
	s_waitcnt lgkmcnt(4)
	v_mfma_f32_32x32x16_bf16 v[32:47], v[212:215], v[220:223], v[32:47]
	ds_read_b128 v[212:215], v96 offset:59936
	s_waitcnt lgkmcnt(4)
	v_mfma_f32_32x32x16_bf16 v[16:31], v[224:227], v[216:219], v[16:31]
	ds_read_b128 v[216:219], v96 offset:55360
	v_mfma_f32_32x32x16_bf16 v[0:15], v[224:227], v[220:223], v[0:15]
	ds_read_b128 v[224:227], v210 offset:18496
	ds_read_b128 v[220:223], v210 offset:23104
	s_waitcnt lgkmcnt(5)
	v_mfma_f32_32x32x16_bf16 v[48:63], v[228:231], v[244:247], v[48:63]
	s_waitcnt lgkmcnt(4)
	v_mfma_f32_32x32x16_bf16 v[32:47], v[228:231], v[252:255], v[32:47]
	ds_read_b128 v[228:231], v96 offset:59968
	s_waitcnt lgkmcnt(4)
	v_mfma_f32_32x32x16_bf16 v[16:31], v[212:215], v[244:247], v[16:31]
	ds_read_b128 v[244:247], v96 offset:55392
	v_mfma_f32_32x32x16_bf16 v[0:15], v[212:215], v[252:255], v[0:15]
	ds_read_b128 v[212:215], v210 offset:18528
	ds_read_b128 v[252:255], v210 offset:23136
	s_waitcnt lgkmcnt(5)
	v_mfma_f32_32x32x16_bf16 v[48:63], v[216:219], v[224:227], v[48:63]
	s_waitcnt vmcnt(15)
	ds_write_b128 v209, v[64:67]
	global_load_dwordx4 v[64:67], v[148:149], off offset:2560
	s_waitcnt lgkmcnt(5)
	v_mfma_f32_32x32x16_bf16 v[32:47], v[216:219], v[220:223], v[32:47]
	ds_read_b128 v[216:219], v96 offset:60000
	s_waitcnt vmcnt(15)
	ds_write_b128 v209, v[72:75] offset:4608
	global_load_dwordx4 v[72:75], v[150:151], off offset:2560
	s_waitcnt lgkmcnt(6)
	v_mfma_f32_32x32x16_bf16 v[16:31], v[228:231], v[224:227], v[16:31]
	s_waitcnt vmcnt(15)
	ds_write_b128 v209, v[76:79] offset:9216
	global_load_dwordx4 v[76:79], v[152:153], off offset:2560
	v_mfma_f32_32x32x16_bf16 v[0:15], v[228:231], v[220:223], v[0:15]
	s_waitcnt vmcnt(15)
	ds_write_b128 v209, v[80:83] offset:13824
	global_load_dwordx4 v[80:83], v[154:155], off offset:2560
	s_waitcnt lgkmcnt(6)
	v_mfma_f32_32x32x16_bf16 v[48:63], v[244:247], v[212:215], v[48:63]
	s_waitcnt vmcnt(15)
	ds_write_b128 v209, v[102:105] offset:36864
	global_load_dwordx4 v[102:105], v[146:147], off offset:2560
	s_waitcnt lgkmcnt(6)
	v_mfma_f32_32x32x16_bf16 v[32:47], v[244:247], v[252:255], v[32:47]
	s_waitcnt vmcnt(15)
	ds_write_b128 v209, v[118:121] offset:41472
	global_load_dwordx4 v[118:121], v[156:157], off offset:2560
	s_waitcnt lgkmcnt(5)
	v_mfma_f32_32x32x16_bf16 v[16:31], v[216:219], v[212:215], v[16:31]
	s_waitcnt vmcnt(15)
	ds_write_b128 v209, v[122:125] offset:46080
	global_load_dwordx4 v[122:125], v[158:159], off offset:2560
	v_mfma_f32_32x32x16_bf16 v[0:15], v[216:219], v[252:255], v[0:15]
	s_waitcnt vmcnt(15)
	ds_write_b128 v209, v[126:129] offset:50688
	global_load_dwordx4 v[126:129], v[160:161], off offset:2560
	s_setprio 0
	s_waitcnt lgkmcnt(0)
	s_barrier
	s_setprio 1
	ds_read_b128 v[212:215], v96 offset:36864
	ds_read_b128 v[216:219], v210
	ds_read_b128 v[220:223], v210 offset:4608
	ds_read_b128 v[224:227], v96 offset:41472
	ds_read_b128 v[228:231], v96 offset:36896
	ds_read_b128 v[244:247], v210 offset:32
	ds_read_b128 v[252:255], v210 offset:4640
	s_waitcnt lgkmcnt(5)
	v_mfma_f32_32x32x16_bf16 v[48:63], v[212:215], v[216:219], v[48:63]
	s_waitcnt lgkmcnt(4)
	v_mfma_f32_32x32x16_bf16 v[32:47], v[212:215], v[220:223], v[32:47]
	ds_read_b128 v[212:215], v96 offset:41504
	s_waitcnt lgkmcnt(4)
	v_mfma_f32_32x32x16_bf16 v[16:31], v[224:227], v[216:219], v[16:31]
	ds_read_b128 v[216:219], v96 offset:36928
	v_mfma_f32_32x32x16_bf16 v[0:15], v[224:227], v[220:223], v[0:15]
	ds_read_b128 v[224:227], v210 offset:64
	ds_read_b128 v[220:223], v210 offset:4672
	s_waitcnt lgkmcnt(5)
	v_mfma_f32_32x32x16_bf16 v[48:63], v[228:231], v[244:247], v[48:63]
	s_waitcnt lgkmcnt(4)
	v_mfma_f32_32x32x16_bf16 v[32:47], v[228:231], v[252:255], v[32:47]
	ds_read_b128 v[228:231], v96 offset:41536
	s_waitcnt lgkmcnt(4)
	v_mfma_f32_32x32x16_bf16 v[16:31], v[212:215], v[244:247], v[16:31]
	ds_read_b128 v[244:247], v96 offset:36960
	v_mfma_f32_32x32x16_bf16 v[0:15], v[212:215], v[252:255], v[0:15]
	ds_read_b128 v[212:215], v210 offset:96
	ds_read_b128 v[252:255], v210 offset:4704
	s_waitcnt lgkmcnt(5)
	v_mfma_f32_32x32x16_bf16 v[48:63], v[216:219], v[224:227], v[48:63]
	s_waitcnt vmcnt(15)
	ds_write_b128 v209, v[68:71] offset:18432
	global_load_dwordx4 v[68:71], v[148:149], off offset:2688
	s_waitcnt lgkmcnt(5)
	v_mfma_f32_32x32x16_bf16 v[32:47], v[216:219], v[220:223], v[32:47]
	ds_read_b128 v[216:219], v96 offset:41568
	s_waitcnt vmcnt(15)
	ds_write_b128 v209, v[84:87] offset:23040
	global_load_dwordx4 v[84:87], v[150:151], off offset:2688
	s_waitcnt lgkmcnt(6)
	v_mfma_f32_32x32x16_bf16 v[16:31], v[228:231], v[224:227], v[16:31]
	s_waitcnt vmcnt(15)
	ds_write_b128 v209, v[88:91] offset:27648
	global_load_dwordx4 v[88:91], v[152:153], off offset:2688
	v_mfma_f32_32x32x16_bf16 v[0:15], v[228:231], v[220:223], v[0:15]
	s_waitcnt vmcnt(15)
	ds_write_b128 v209, v[92:95] offset:32256
	global_load_dwordx4 v[92:95], v[154:155], off offset:2688
	s_waitcnt lgkmcnt(6)
	v_mfma_f32_32x32x16_bf16 v[48:63], v[244:247], v[212:215], v[48:63]
	s_waitcnt vmcnt(15)
	ds_write_b128 v209, v[98:101] offset:55296
	global_load_dwordx4 v[98:101], v[146:147], off offset:2688
	s_waitcnt lgkmcnt(6)
	v_mfma_f32_32x32x16_bf16 v[32:47], v[244:247], v[252:255], v[32:47]
	s_waitcnt vmcnt(15)
	ds_write_b128 v209, v[106:109] offset:59904
	global_load_dwordx4 v[106:109], v[156:157], off offset:2688
	s_waitcnt lgkmcnt(5)
	v_mfma_f32_32x32x16_bf16 v[16:31], v[216:219], v[212:215], v[16:31]
	s_waitcnt vmcnt(15)
	ds_write_b128 v209, v[110:113] offset:64512
	global_load_dwordx4 v[110:113], v[158:159], off offset:2688
	v_mfma_f32_32x32x16_bf16 v[0:15], v[216:219], v[252:255], v[0:15]
	s_waitcnt vmcnt(15)
	ds_write_b128 v211, v[114:117] offset:13824
	global_load_dwordx4 v[114:117], v[160:161], off offset:2688
	s_setprio 0
	s_waitcnt lgkmcnt(0)
	s_barrier
	s_setprio 1
	ds_read_b128 v[212:215], v96 offset:55296
	ds_read_b128 v[216:219], v210 offset:18432
	ds_read_b128 v[220:223], v210 offset:23040
	ds_read_b128 v[224:227], v96 offset:59904
	ds_read_b128 v[228:231], v96 offset:55328
	ds_read_b128 v[244:247], v210 offset:18464
	ds_read_b128 v[252:255], v210 offset:23072
	s_waitcnt lgkmcnt(5)
	v_mfma_f32_32x32x16_bf16 v[48:63], v[212:215], v[216:219], v[48:63]
	s_waitcnt lgkmcnt(4)
	v_mfma_f32_32x32x16_bf16 v[32:47], v[212:215], v[220:223], v[32:47]
	ds_read_b128 v[212:215], v96 offset:59936
	s_waitcnt lgkmcnt(4)
	v_mfma_f32_32x32x16_bf16 v[16:31], v[224:227], v[216:219], v[16:31]
	ds_read_b128 v[216:219], v96 offset:55360
	v_mfma_f32_32x32x16_bf16 v[0:15], v[224:227], v[220:223], v[0:15]
	ds_read_b128 v[224:227], v210 offset:18496
	ds_read_b128 v[220:223], v210 offset:23104
	s_waitcnt lgkmcnt(5)
	v_mfma_f32_32x32x16_bf16 v[48:63], v[228:231], v[244:247], v[48:63]
	s_waitcnt lgkmcnt(4)
	v_mfma_f32_32x32x16_bf16 v[32:47], v[228:231], v[252:255], v[32:47]
	ds_read_b128 v[228:231], v96 offset:59968
	s_waitcnt lgkmcnt(4)
	v_mfma_f32_32x32x16_bf16 v[16:31], v[212:215], v[244:247], v[16:31]
	ds_read_b128 v[244:247], v96 offset:55392
	v_mfma_f32_32x32x16_bf16 v[0:15], v[212:215], v[252:255], v[0:15]
	ds_read_b128 v[212:215], v210 offset:18528
	ds_read_b128 v[252:255], v210 offset:23136
	s_waitcnt lgkmcnt(5)
	v_mfma_f32_32x32x16_bf16 v[48:63], v[216:219], v[224:227], v[48:63]
	s_waitcnt vmcnt(15)
	ds_write_b128 v209, v[64:67]
	global_load_dwordx4 v[64:67], v[148:149], off offset:2816
	s_waitcnt lgkmcnt(5)
	v_mfma_f32_32x32x16_bf16 v[32:47], v[216:219], v[220:223], v[32:47]
	ds_read_b128 v[216:219], v96 offset:60000
	s_waitcnt vmcnt(15)
	ds_write_b128 v209, v[72:75] offset:4608
	global_load_dwordx4 v[72:75], v[150:151], off offset:2816
	s_waitcnt lgkmcnt(6)
	v_mfma_f32_32x32x16_bf16 v[16:31], v[228:231], v[224:227], v[16:31]
	s_waitcnt vmcnt(15)
	ds_write_b128 v209, v[76:79] offset:9216
	global_load_dwordx4 v[76:79], v[152:153], off offset:2816
	v_mfma_f32_32x32x16_bf16 v[0:15], v[228:231], v[220:223], v[0:15]
	s_waitcnt vmcnt(15)
	ds_write_b128 v209, v[80:83] offset:13824
	global_load_dwordx4 v[80:83], v[154:155], off offset:2816
	s_waitcnt lgkmcnt(6)
	v_mfma_f32_32x32x16_bf16 v[48:63], v[244:247], v[212:215], v[48:63]
	s_waitcnt vmcnt(15)
	ds_write_b128 v209, v[102:105] offset:36864
	global_load_dwordx4 v[102:105], v[146:147], off offset:2816
	s_waitcnt lgkmcnt(6)
	v_mfma_f32_32x32x16_bf16 v[32:47], v[244:247], v[252:255], v[32:47]
	s_waitcnt vmcnt(15)
	ds_write_b128 v209, v[118:121] offset:41472
	global_load_dwordx4 v[118:121], v[156:157], off offset:2816
	s_waitcnt lgkmcnt(5)
	v_mfma_f32_32x32x16_bf16 v[16:31], v[216:219], v[212:215], v[16:31]
	s_waitcnt vmcnt(15)
	ds_write_b128 v209, v[122:125] offset:46080
	global_load_dwordx4 v[122:125], v[158:159], off offset:2816
	v_mfma_f32_32x32x16_bf16 v[0:15], v[216:219], v[252:255], v[0:15]
	s_waitcnt vmcnt(15)
	ds_write_b128 v209, v[126:129] offset:50688
	global_load_dwordx4 v[126:129], v[160:161], off offset:2816
	s_setprio 0
	s_waitcnt lgkmcnt(0)
	s_barrier
	s_setprio 1
	ds_read_b128 v[212:215], v96 offset:36864
	ds_read_b128 v[216:219], v210
	ds_read_b128 v[220:223], v210 offset:4608
	ds_read_b128 v[224:227], v96 offset:41472
	ds_read_b128 v[228:231], v96 offset:36896
	ds_read_b128 v[244:247], v210 offset:32
	ds_read_b128 v[252:255], v210 offset:4640
	s_waitcnt lgkmcnt(5)
	v_mfma_f32_32x32x16_bf16 v[48:63], v[212:215], v[216:219], v[48:63]
	s_waitcnt lgkmcnt(4)
	v_mfma_f32_32x32x16_bf16 v[32:47], v[212:215], v[220:223], v[32:47]
	ds_read_b128 v[212:215], v96 offset:41504
	s_waitcnt lgkmcnt(4)
	v_mfma_f32_32x32x16_bf16 v[16:31], v[224:227], v[216:219], v[16:31]
	ds_read_b128 v[216:219], v96 offset:36928
	v_mfma_f32_32x32x16_bf16 v[0:15], v[224:227], v[220:223], v[0:15]
	ds_read_b128 v[224:227], v210 offset:64
	ds_read_b128 v[220:223], v210 offset:4672
	s_waitcnt lgkmcnt(5)
	v_mfma_f32_32x32x16_bf16 v[48:63], v[228:231], v[244:247], v[48:63]
	s_waitcnt lgkmcnt(4)
	v_mfma_f32_32x32x16_bf16 v[32:47], v[228:231], v[252:255], v[32:47]
	ds_read_b128 v[228:231], v96 offset:41536
	s_waitcnt lgkmcnt(4)
	v_mfma_f32_32x32x16_bf16 v[16:31], v[212:215], v[244:247], v[16:31]
	ds_read_b128 v[244:247], v96 offset:36960
	v_mfma_f32_32x32x16_bf16 v[0:15], v[212:215], v[252:255], v[0:15]
	ds_read_b128 v[212:215], v210 offset:96
	ds_read_b128 v[252:255], v210 offset:4704
	s_waitcnt lgkmcnt(5)
	v_mfma_f32_32x32x16_bf16 v[48:63], v[216:219], v[224:227], v[48:63]
	s_waitcnt vmcnt(15)
	ds_write_b128 v209, v[68:71] offset:18432
	global_load_dwordx4 v[68:71], v[148:149], off offset:2944
	s_waitcnt lgkmcnt(5)
	v_mfma_f32_32x32x16_bf16 v[32:47], v[216:219], v[220:223], v[32:47]
	ds_read_b128 v[216:219], v96 offset:41568
	s_waitcnt vmcnt(15)
	ds_write_b128 v209, v[84:87] offset:23040
	global_load_dwordx4 v[84:87], v[150:151], off offset:2944
	s_waitcnt lgkmcnt(6)
	v_mfma_f32_32x32x16_bf16 v[16:31], v[228:231], v[224:227], v[16:31]
	s_waitcnt vmcnt(15)
	ds_write_b128 v209, v[88:91] offset:27648
	global_load_dwordx4 v[88:91], v[152:153], off offset:2944
	v_mfma_f32_32x32x16_bf16 v[0:15], v[228:231], v[220:223], v[0:15]
	s_waitcnt vmcnt(15)
	ds_write_b128 v209, v[92:95] offset:32256
	global_load_dwordx4 v[92:95], v[154:155], off offset:2944
	s_waitcnt lgkmcnt(6)
	v_mfma_f32_32x32x16_bf16 v[48:63], v[244:247], v[212:215], v[48:63]
	s_waitcnt vmcnt(15)
	ds_write_b128 v209, v[98:101] offset:55296
	global_load_dwordx4 v[98:101], v[146:147], off offset:2944
	s_waitcnt lgkmcnt(6)
	v_mfma_f32_32x32x16_bf16 v[32:47], v[244:247], v[252:255], v[32:47]
	s_waitcnt vmcnt(15)
	ds_write_b128 v209, v[106:109] offset:59904
	global_load_dwordx4 v[106:109], v[156:157], off offset:2944
	s_waitcnt lgkmcnt(5)
	v_mfma_f32_32x32x16_bf16 v[16:31], v[216:219], v[212:215], v[16:31]
	s_waitcnt vmcnt(15)
	ds_write_b128 v209, v[110:113] offset:64512
	global_load_dwordx4 v[110:113], v[158:159], off offset:2944
	v_mfma_f32_32x32x16_bf16 v[0:15], v[216:219], v[252:255], v[0:15]
	s_waitcnt vmcnt(15)
	ds_write_b128 v211, v[114:117] offset:13824
	global_load_dwordx4 v[114:117], v[160:161], off offset:2944
	s_setprio 0
	s_waitcnt lgkmcnt(0)
	s_barrier
	s_setprio 1
	ds_read_b128 v[212:215], v96 offset:55296
	ds_read_b128 v[216:219], v210 offset:18432
	ds_read_b128 v[220:223], v210 offset:23040
	ds_read_b128 v[224:227], v96 offset:59904
	ds_read_b128 v[228:231], v96 offset:55328
	ds_read_b128 v[244:247], v210 offset:18464
	ds_read_b128 v[252:255], v210 offset:23072
	s_waitcnt lgkmcnt(5)
	v_mfma_f32_32x32x16_bf16 v[48:63], v[212:215], v[216:219], v[48:63]
	s_waitcnt lgkmcnt(4)
	v_mfma_f32_32x32x16_bf16 v[32:47], v[212:215], v[220:223], v[32:47]
	ds_read_b128 v[212:215], v96 offset:59936
	s_waitcnt lgkmcnt(4)
	v_mfma_f32_32x32x16_bf16 v[16:31], v[224:227], v[216:219], v[16:31]
	ds_read_b128 v[216:219], v96 offset:55360
	v_mfma_f32_32x32x16_bf16 v[0:15], v[224:227], v[220:223], v[0:15]
	ds_read_b128 v[224:227], v210 offset:18496
	ds_read_b128 v[220:223], v210 offset:23104
	s_waitcnt lgkmcnt(5)
	v_mfma_f32_32x32x16_bf16 v[48:63], v[228:231], v[244:247], v[48:63]
	s_waitcnt lgkmcnt(4)
	v_mfma_f32_32x32x16_bf16 v[32:47], v[228:231], v[252:255], v[32:47]
	ds_read_b128 v[228:231], v96 offset:59968
	s_waitcnt lgkmcnt(4)
	v_mfma_f32_32x32x16_bf16 v[16:31], v[212:215], v[244:247], v[16:31]
	ds_read_b128 v[244:247], v96 offset:55392
	v_mfma_f32_32x32x16_bf16 v[0:15], v[212:215], v[252:255], v[0:15]
	ds_read_b128 v[212:215], v210 offset:18528
	ds_read_b128 v[252:255], v210 offset:23136
	s_waitcnt lgkmcnt(5)
	v_mfma_f32_32x32x16_bf16 v[48:63], v[216:219], v[224:227], v[48:63]
	s_waitcnt vmcnt(15)
	ds_write_b128 v209, v[64:67]
	global_load_dwordx4 v[64:67], v[148:149], off offset:3072
	s_waitcnt lgkmcnt(5)
	v_mfma_f32_32x32x16_bf16 v[32:47], v[216:219], v[220:223], v[32:47]
	ds_read_b128 v[216:219], v96 offset:60000
	s_waitcnt vmcnt(15)
	ds_write_b128 v209, v[72:75] offset:4608
	global_load_dwordx4 v[72:75], v[150:151], off offset:3072
	s_waitcnt lgkmcnt(6)
	v_mfma_f32_32x32x16_bf16 v[16:31], v[228:231], v[224:227], v[16:31]
	s_waitcnt vmcnt(15)
	ds_write_b128 v209, v[76:79] offset:9216
	global_load_dwordx4 v[76:79], v[152:153], off offset:3072
	v_mfma_f32_32x32x16_bf16 v[0:15], v[228:231], v[220:223], v[0:15]
	s_waitcnt vmcnt(15)
	ds_write_b128 v209, v[80:83] offset:13824
	global_load_dwordx4 v[80:83], v[154:155], off offset:3072
	s_waitcnt lgkmcnt(6)
	v_mfma_f32_32x32x16_bf16 v[48:63], v[244:247], v[212:215], v[48:63]
	s_waitcnt vmcnt(15)
	ds_write_b128 v209, v[102:105] offset:36864
	global_load_dwordx4 v[102:105], v[146:147], off offset:3072
	s_waitcnt lgkmcnt(6)
	v_mfma_f32_32x32x16_bf16 v[32:47], v[244:247], v[252:255], v[32:47]
	s_waitcnt vmcnt(15)
	ds_write_b128 v209, v[118:121] offset:41472
	global_load_dwordx4 v[118:121], v[156:157], off offset:3072
	s_waitcnt lgkmcnt(5)
	v_mfma_f32_32x32x16_bf16 v[16:31], v[216:219], v[212:215], v[16:31]
	s_waitcnt vmcnt(15)
	ds_write_b128 v209, v[122:125] offset:46080
	global_load_dwordx4 v[122:125], v[158:159], off offset:3072
	v_mfma_f32_32x32x16_bf16 v[0:15], v[216:219], v[252:255], v[0:15]
	s_waitcnt vmcnt(15)
	ds_write_b128 v209, v[126:129] offset:50688
	global_load_dwordx4 v[126:129], v[160:161], off offset:3072
	s_setprio 0
	s_waitcnt lgkmcnt(0)
	s_barrier
	s_setprio 1
	ds_read_b128 v[212:215], v96 offset:36864
	ds_read_b128 v[216:219], v210
	ds_read_b128 v[220:223], v210 offset:4608
	ds_read_b128 v[224:227], v96 offset:41472
	ds_read_b128 v[228:231], v96 offset:36896
	ds_read_b128 v[244:247], v210 offset:32
	ds_read_b128 v[252:255], v210 offset:4640
	s_waitcnt lgkmcnt(5)
	v_mfma_f32_32x32x16_bf16 v[48:63], v[212:215], v[216:219], v[48:63]
	s_waitcnt lgkmcnt(4)
	v_mfma_f32_32x32x16_bf16 v[32:47], v[212:215], v[220:223], v[32:47]
	ds_read_b128 v[212:215], v96 offset:41504
	s_waitcnt lgkmcnt(4)
	v_mfma_f32_32x32x16_bf16 v[16:31], v[224:227], v[216:219], v[16:31]
	ds_read_b128 v[216:219], v96 offset:36928
	v_mfma_f32_32x32x16_bf16 v[0:15], v[224:227], v[220:223], v[0:15]
	ds_read_b128 v[224:227], v210 offset:64
	ds_read_b128 v[220:223], v210 offset:4672
	s_waitcnt lgkmcnt(5)
	v_mfma_f32_32x32x16_bf16 v[48:63], v[228:231], v[244:247], v[48:63]
	s_waitcnt lgkmcnt(4)
	v_mfma_f32_32x32x16_bf16 v[32:47], v[228:231], v[252:255], v[32:47]
	ds_read_b128 v[228:231], v96 offset:41536
	s_waitcnt lgkmcnt(4)
	v_mfma_f32_32x32x16_bf16 v[16:31], v[212:215], v[244:247], v[16:31]
	ds_read_b128 v[244:247], v96 offset:36960
	v_mfma_f32_32x32x16_bf16 v[0:15], v[212:215], v[252:255], v[0:15]
	ds_read_b128 v[212:215], v210 offset:96
	ds_read_b128 v[252:255], v210 offset:4704
	s_waitcnt lgkmcnt(5)
	v_mfma_f32_32x32x16_bf16 v[48:63], v[216:219], v[224:227], v[48:63]
	s_waitcnt vmcnt(15)
	ds_write_b128 v209, v[68:71] offset:18432
	global_load_dwordx4 v[68:71], v[148:149], off offset:3200
	s_waitcnt lgkmcnt(5)
	v_mfma_f32_32x32x16_bf16 v[32:47], v[216:219], v[220:223], v[32:47]
	ds_read_b128 v[216:219], v96 offset:41568
	s_waitcnt vmcnt(15)
	ds_write_b128 v209, v[84:87] offset:23040
	global_load_dwordx4 v[84:87], v[150:151], off offset:3200
	s_waitcnt lgkmcnt(6)
	v_mfma_f32_32x32x16_bf16 v[16:31], v[228:231], v[224:227], v[16:31]
	s_waitcnt vmcnt(15)
	ds_write_b128 v209, v[88:91] offset:27648
	global_load_dwordx4 v[88:91], v[152:153], off offset:3200
	v_mfma_f32_32x32x16_bf16 v[0:15], v[228:231], v[220:223], v[0:15]
	s_waitcnt vmcnt(15)
	ds_write_b128 v209, v[92:95] offset:32256
	global_load_dwordx4 v[92:95], v[154:155], off offset:3200
	s_waitcnt lgkmcnt(6)
	v_mfma_f32_32x32x16_bf16 v[48:63], v[244:247], v[212:215], v[48:63]
	s_waitcnt vmcnt(15)
	ds_write_b128 v209, v[98:101] offset:55296
	global_load_dwordx4 v[98:101], v[146:147], off offset:3200
	s_waitcnt lgkmcnt(6)
	v_mfma_f32_32x32x16_bf16 v[32:47], v[244:247], v[252:255], v[32:47]
	s_waitcnt vmcnt(15)
	ds_write_b128 v209, v[106:109] offset:59904
	global_load_dwordx4 v[106:109], v[156:157], off offset:3200
	s_waitcnt lgkmcnt(5)
	v_mfma_f32_32x32x16_bf16 v[16:31], v[216:219], v[212:215], v[16:31]
	s_waitcnt vmcnt(15)
	ds_write_b128 v209, v[110:113] offset:64512
	global_load_dwordx4 v[110:113], v[158:159], off offset:3200
	v_mfma_f32_32x32x16_bf16 v[0:15], v[216:219], v[252:255], v[0:15]
	s_waitcnt vmcnt(15)
	ds_write_b128 v211, v[114:117] offset:13824
	global_load_dwordx4 v[114:117], v[160:161], off offset:3200
	s_setprio 0
	s_waitcnt lgkmcnt(0)
	s_barrier
	s_setprio 1
	ds_read_b128 v[212:215], v96 offset:55296
	ds_read_b128 v[216:219], v210 offset:18432
	ds_read_b128 v[220:223], v210 offset:23040
	ds_read_b128 v[224:227], v96 offset:59904
	ds_read_b128 v[228:231], v96 offset:55328
	ds_read_b128 v[244:247], v210 offset:18464
	ds_read_b128 v[252:255], v210 offset:23072
	s_waitcnt lgkmcnt(5)
	v_mfma_f32_32x32x16_bf16 v[48:63], v[212:215], v[216:219], v[48:63]
	s_waitcnt lgkmcnt(4)
	v_mfma_f32_32x32x16_bf16 v[32:47], v[212:215], v[220:223], v[32:47]
	ds_read_b128 v[212:215], v96 offset:59936
	s_waitcnt lgkmcnt(4)
	v_mfma_f32_32x32x16_bf16 v[16:31], v[224:227], v[216:219], v[16:31]
	ds_read_b128 v[216:219], v96 offset:55360
	v_mfma_f32_32x32x16_bf16 v[0:15], v[224:227], v[220:223], v[0:15]
	ds_read_b128 v[224:227], v210 offset:18496
	ds_read_b128 v[220:223], v210 offset:23104
	s_waitcnt lgkmcnt(5)
	v_mfma_f32_32x32x16_bf16 v[48:63], v[228:231], v[244:247], v[48:63]
	s_waitcnt lgkmcnt(4)
	v_mfma_f32_32x32x16_bf16 v[32:47], v[228:231], v[252:255], v[32:47]
	ds_read_b128 v[228:231], v96 offset:59968
	s_waitcnt lgkmcnt(4)
	v_mfma_f32_32x32x16_bf16 v[16:31], v[212:215], v[244:247], v[16:31]
	ds_read_b128 v[244:247], v96 offset:55392
	v_mfma_f32_32x32x16_bf16 v[0:15], v[212:215], v[252:255], v[0:15]
	ds_read_b128 v[212:215], v210 offset:18528
	ds_read_b128 v[252:255], v210 offset:23136
	s_waitcnt lgkmcnt(5)
	v_mfma_f32_32x32x16_bf16 v[48:63], v[216:219], v[224:227], v[48:63]
	s_waitcnt vmcnt(15)
	ds_write_b128 v209, v[64:67]
	global_load_dwordx4 v[64:67], v[148:149], off offset:3328
	s_waitcnt lgkmcnt(5)
	v_mfma_f32_32x32x16_bf16 v[32:47], v[216:219], v[220:223], v[32:47]
	ds_read_b128 v[216:219], v96 offset:60000
	s_waitcnt vmcnt(15)
	ds_write_b128 v209, v[72:75] offset:4608
	global_load_dwordx4 v[72:75], v[150:151], off offset:3328
	s_waitcnt lgkmcnt(6)
	v_mfma_f32_32x32x16_bf16 v[16:31], v[228:231], v[224:227], v[16:31]
	s_waitcnt vmcnt(15)
	ds_write_b128 v209, v[76:79] offset:9216
	global_load_dwordx4 v[76:79], v[152:153], off offset:3328
	v_mfma_f32_32x32x16_bf16 v[0:15], v[228:231], v[220:223], v[0:15]
	s_waitcnt vmcnt(15)
	ds_write_b128 v209, v[80:83] offset:13824
	global_load_dwordx4 v[80:83], v[154:155], off offset:3328
	s_waitcnt lgkmcnt(6)
	v_mfma_f32_32x32x16_bf16 v[48:63], v[244:247], v[212:215], v[48:63]
	s_waitcnt vmcnt(15)
	ds_write_b128 v209, v[102:105] offset:36864
	global_load_dwordx4 v[102:105], v[146:147], off offset:3328
	s_waitcnt lgkmcnt(6)
	v_mfma_f32_32x32x16_bf16 v[32:47], v[244:247], v[252:255], v[32:47]
	s_waitcnt vmcnt(15)
	ds_write_b128 v209, v[118:121] offset:41472
	global_load_dwordx4 v[118:121], v[156:157], off offset:3328
	s_waitcnt lgkmcnt(5)
	v_mfma_f32_32x32x16_bf16 v[16:31], v[216:219], v[212:215], v[16:31]
	s_waitcnt vmcnt(15)
	ds_write_b128 v209, v[122:125] offset:46080
	global_load_dwordx4 v[122:125], v[158:159], off offset:3328
	v_mfma_f32_32x32x16_bf16 v[0:15], v[216:219], v[252:255], v[0:15]
	s_waitcnt vmcnt(15)
	ds_write_b128 v209, v[126:129] offset:50688
	global_load_dwordx4 v[126:129], v[160:161], off offset:3328
	s_setprio 0
	s_waitcnt lgkmcnt(0)
	s_barrier
	s_setprio 1
	ds_read_b128 v[212:215], v96 offset:36864
	ds_read_b128 v[216:219], v210
	ds_read_b128 v[220:223], v210 offset:4608
	ds_read_b128 v[224:227], v96 offset:41472
	ds_read_b128 v[228:231], v96 offset:36896
	ds_read_b128 v[244:247], v210 offset:32
	ds_read_b128 v[252:255], v210 offset:4640
	s_waitcnt lgkmcnt(5)
	v_mfma_f32_32x32x16_bf16 v[48:63], v[212:215], v[216:219], v[48:63]
	s_waitcnt lgkmcnt(4)
	v_mfma_f32_32x32x16_bf16 v[32:47], v[212:215], v[220:223], v[32:47]
	ds_read_b128 v[212:215], v96 offset:41504
	s_waitcnt lgkmcnt(4)
	v_mfma_f32_32x32x16_bf16 v[16:31], v[224:227], v[216:219], v[16:31]
	ds_read_b128 v[216:219], v96 offset:36928
	v_mfma_f32_32x32x16_bf16 v[0:15], v[224:227], v[220:223], v[0:15]
	ds_read_b128 v[224:227], v210 offset:64
	ds_read_b128 v[220:223], v210 offset:4672
	s_waitcnt lgkmcnt(5)
	v_mfma_f32_32x32x16_bf16 v[48:63], v[228:231], v[244:247], v[48:63]
	s_waitcnt lgkmcnt(4)
	v_mfma_f32_32x32x16_bf16 v[32:47], v[228:231], v[252:255], v[32:47]
	ds_read_b128 v[228:231], v96 offset:41536
	s_waitcnt lgkmcnt(4)
	v_mfma_f32_32x32x16_bf16 v[16:31], v[212:215], v[244:247], v[16:31]
	ds_read_b128 v[244:247], v96 offset:36960
	v_mfma_f32_32x32x16_bf16 v[0:15], v[212:215], v[252:255], v[0:15]
	ds_read_b128 v[212:215], v210 offset:96
	ds_read_b128 v[252:255], v210 offset:4704
	s_waitcnt lgkmcnt(5)
	v_mfma_f32_32x32x16_bf16 v[48:63], v[216:219], v[224:227], v[48:63]
	s_waitcnt vmcnt(15)
	ds_write_b128 v209, v[68:71] offset:18432
	global_load_dwordx4 v[68:71], v[148:149], off offset:3456
	s_waitcnt lgkmcnt(5)
	v_mfma_f32_32x32x16_bf16 v[32:47], v[216:219], v[220:223], v[32:47]
	ds_read_b128 v[216:219], v96 offset:41568
	s_waitcnt vmcnt(15)
	ds_write_b128 v209, v[84:87] offset:23040
	global_load_dwordx4 v[84:87], v[150:151], off offset:3456
	s_waitcnt lgkmcnt(6)
	v_mfma_f32_32x32x16_bf16 v[16:31], v[228:231], v[224:227], v[16:31]
	s_waitcnt vmcnt(15)
	ds_write_b128 v209, v[88:91] offset:27648
	global_load_dwordx4 v[88:91], v[152:153], off offset:3456
	v_mfma_f32_32x32x16_bf16 v[0:15], v[228:231], v[220:223], v[0:15]
	s_waitcnt vmcnt(15)
	ds_write_b128 v209, v[92:95] offset:32256
	global_load_dwordx4 v[92:95], v[154:155], off offset:3456
	s_waitcnt lgkmcnt(6)
	v_mfma_f32_32x32x16_bf16 v[48:63], v[244:247], v[212:215], v[48:63]
	s_waitcnt vmcnt(15)
	ds_write_b128 v209, v[98:101] offset:55296
	global_load_dwordx4 v[98:101], v[146:147], off offset:3456
	s_waitcnt lgkmcnt(6)
	v_mfma_f32_32x32x16_bf16 v[32:47], v[244:247], v[252:255], v[32:47]
	s_waitcnt vmcnt(15)
	ds_write_b128 v209, v[106:109] offset:59904
	global_load_dwordx4 v[106:109], v[156:157], off offset:3456
	s_waitcnt lgkmcnt(5)
	v_mfma_f32_32x32x16_bf16 v[16:31], v[216:219], v[212:215], v[16:31]
	s_waitcnt vmcnt(15)
	ds_write_b128 v209, v[110:113] offset:64512
	global_load_dwordx4 v[110:113], v[158:159], off offset:3456
	v_mfma_f32_32x32x16_bf16 v[0:15], v[216:219], v[252:255], v[0:15]
	s_waitcnt vmcnt(15)
	ds_write_b128 v211, v[114:117] offset:13824
	global_load_dwordx4 v[114:117], v[160:161], off offset:3456
	s_setprio 0
	s_waitcnt lgkmcnt(0)
	s_barrier
	s_setprio 1
	ds_read_b128 v[212:215], v96 offset:55296
	ds_read_b128 v[216:219], v210 offset:18432
	ds_read_b128 v[220:223], v210 offset:23040
	ds_read_b128 v[224:227], v96 offset:59904
	ds_read_b128 v[228:231], v96 offset:55328
	ds_read_b128 v[244:247], v210 offset:18464
	ds_read_b128 v[252:255], v210 offset:23072
	s_waitcnt lgkmcnt(5)
	v_mfma_f32_32x32x16_bf16 v[48:63], v[212:215], v[216:219], v[48:63]
	s_waitcnt lgkmcnt(4)
	v_mfma_f32_32x32x16_bf16 v[32:47], v[212:215], v[220:223], v[32:47]
	ds_read_b128 v[212:215], v96 offset:59936
	s_waitcnt lgkmcnt(4)
	v_mfma_f32_32x32x16_bf16 v[16:31], v[224:227], v[216:219], v[16:31]
	ds_read_b128 v[216:219], v96 offset:55360
	v_mfma_f32_32x32x16_bf16 v[0:15], v[224:227], v[220:223], v[0:15]
	ds_read_b128 v[224:227], v210 offset:18496
	ds_read_b128 v[220:223], v210 offset:23104
	s_waitcnt lgkmcnt(5)
	v_mfma_f32_32x32x16_bf16 v[48:63], v[228:231], v[244:247], v[48:63]
	s_waitcnt lgkmcnt(4)
	v_mfma_f32_32x32x16_bf16 v[32:47], v[228:231], v[252:255], v[32:47]
	ds_read_b128 v[228:231], v96 offset:59968
	s_waitcnt lgkmcnt(4)
	v_mfma_f32_32x32x16_bf16 v[16:31], v[212:215], v[244:247], v[16:31]
	ds_read_b128 v[244:247], v96 offset:55392
	v_mfma_f32_32x32x16_bf16 v[0:15], v[212:215], v[252:255], v[0:15]
	ds_read_b128 v[212:215], v210 offset:18528
	ds_read_b128 v[252:255], v210 offset:23136
	s_waitcnt lgkmcnt(5)
	v_mfma_f32_32x32x16_bf16 v[48:63], v[216:219], v[224:227], v[48:63]
	s_waitcnt vmcnt(15)
	ds_write_b128 v209, v[64:67]
	global_load_dwordx4 v[64:67], v[148:149], off offset:3584
	s_waitcnt lgkmcnt(5)
	v_mfma_f32_32x32x16_bf16 v[32:47], v[216:219], v[220:223], v[32:47]
	ds_read_b128 v[216:219], v96 offset:60000
	s_waitcnt vmcnt(15)
	ds_write_b128 v209, v[72:75] offset:4608
	global_load_dwordx4 v[72:75], v[150:151], off offset:3584
	s_waitcnt lgkmcnt(6)
	v_mfma_f32_32x32x16_bf16 v[16:31], v[228:231], v[224:227], v[16:31]
	s_waitcnt vmcnt(15)
	ds_write_b128 v209, v[76:79] offset:9216
	global_load_dwordx4 v[76:79], v[152:153], off offset:3584
	v_mfma_f32_32x32x16_bf16 v[0:15], v[228:231], v[220:223], v[0:15]
	s_waitcnt vmcnt(15)
	ds_write_b128 v209, v[80:83] offset:13824
	global_load_dwordx4 v[80:83], v[154:155], off offset:3584
	s_waitcnt lgkmcnt(6)
	v_mfma_f32_32x32x16_bf16 v[48:63], v[244:247], v[212:215], v[48:63]
	s_waitcnt vmcnt(15)
	ds_write_b128 v209, v[102:105] offset:36864
	global_load_dwordx4 v[102:105], v[146:147], off offset:3584
	s_waitcnt lgkmcnt(6)
	v_mfma_f32_32x32x16_bf16 v[32:47], v[244:247], v[252:255], v[32:47]
	s_waitcnt vmcnt(15)
	ds_write_b128 v209, v[118:121] offset:41472
	global_load_dwordx4 v[118:121], v[156:157], off offset:3584
	s_waitcnt lgkmcnt(5)
	v_mfma_f32_32x32x16_bf16 v[16:31], v[216:219], v[212:215], v[16:31]
	s_waitcnt vmcnt(15)
	ds_write_b128 v209, v[122:125] offset:46080
	global_load_dwordx4 v[122:125], v[158:159], off offset:3584
	v_mfma_f32_32x32x16_bf16 v[0:15], v[216:219], v[252:255], v[0:15]
	s_waitcnt vmcnt(15)
	ds_write_b128 v209, v[126:129] offset:50688
	global_load_dwordx4 v[126:129], v[160:161], off offset:3584
	s_setprio 0
	s_waitcnt lgkmcnt(0)
	s_barrier
	s_setprio 1
	ds_read_b128 v[212:215], v96 offset:36864
	ds_read_b128 v[216:219], v210
	ds_read_b128 v[220:223], v210 offset:4608
	ds_read_b128 v[224:227], v96 offset:41472
	ds_read_b128 v[228:231], v96 offset:36896
	ds_read_b128 v[244:247], v210 offset:32
	ds_read_b128 v[252:255], v210 offset:4640
	s_waitcnt lgkmcnt(5)
	v_mfma_f32_32x32x16_bf16 v[48:63], v[212:215], v[216:219], v[48:63]
	s_waitcnt lgkmcnt(4)
	v_mfma_f32_32x32x16_bf16 v[32:47], v[212:215], v[220:223], v[32:47]
	ds_read_b128 v[212:215], v96 offset:41504
	s_waitcnt lgkmcnt(4)
	v_mfma_f32_32x32x16_bf16 v[16:31], v[224:227], v[216:219], v[16:31]
	ds_read_b128 v[216:219], v96 offset:36928
	v_mfma_f32_32x32x16_bf16 v[0:15], v[224:227], v[220:223], v[0:15]
	ds_read_b128 v[224:227], v210 offset:64
	ds_read_b128 v[220:223], v210 offset:4672
	s_waitcnt lgkmcnt(5)
	v_mfma_f32_32x32x16_bf16 v[48:63], v[228:231], v[244:247], v[48:63]
	s_waitcnt lgkmcnt(4)
	v_mfma_f32_32x32x16_bf16 v[32:47], v[228:231], v[252:255], v[32:47]
	ds_read_b128 v[228:231], v96 offset:41536
	s_waitcnt lgkmcnt(4)
	v_mfma_f32_32x32x16_bf16 v[16:31], v[212:215], v[244:247], v[16:31]
	ds_read_b128 v[244:247], v96 offset:36960
	v_mfma_f32_32x32x16_bf16 v[0:15], v[212:215], v[252:255], v[0:15]
	ds_read_b128 v[212:215], v210 offset:96
	ds_read_b128 v[252:255], v210 offset:4704
	s_waitcnt lgkmcnt(5)
	v_mfma_f32_32x32x16_bf16 v[48:63], v[216:219], v[224:227], v[48:63]
	s_waitcnt vmcnt(15)
	ds_write_b128 v209, v[68:71] offset:18432
	global_load_dwordx4 v[68:71], v[148:149], off offset:3712
	s_waitcnt vmcnt(15)
	s_waitcnt lgkmcnt(5)
	v_mfma_f32_32x32x16_bf16 v[32:47], v[216:219], v[220:223], v[32:47]
	ds_read_b128 v[216:219], v96 offset:41568
	ds_write_b128 v209, v[84:87] offset:23040
	global_load_dwordx4 v[84:87], v[150:151], off offset:3712
	s_waitcnt vmcnt(15)
	s_waitcnt lgkmcnt(6)
	v_mfma_f32_32x32x16_bf16 v[16:31], v[228:231], v[224:227], v[16:31]
	ds_write_b128 v209, v[88:91] offset:27648
	global_load_dwordx4 v[88:91], v[152:153], off offset:3712
	s_waitcnt vmcnt(15)
	v_mfma_f32_32x32x16_bf16 v[0:15], v[228:231], v[220:223], v[0:15]
	ds_write_b128 v209, v[92:95] offset:32256
	global_load_dwordx4 v[92:95], v[154:155], off offset:3712
	s_waitcnt vmcnt(15)
	s_waitcnt lgkmcnt(6)
	v_mfma_f32_32x32x16_bf16 v[48:63], v[244:247], v[212:215], v[48:63]
	ds_write_b128 v209, v[98:101] offset:55296
	s_waitcnt vmcnt(14)
	ds_write_b128 v209, v[106:109] offset:59904
	s_waitcnt lgkmcnt(7)
	v_mfma_f32_32x32x16_bf16 v[32:47], v[244:247], v[252:255], v[32:47]
	s_waitcnt vmcnt(13)
	ds_write_b128 v209, v[110:113] offset:64512
	s_waitcnt vmcnt(12)
	ds_write_b128 v211, v[114:117] offset:13824
	s_waitcnt lgkmcnt(7)
	v_mfma_f32_32x32x16_bf16 v[16:31], v[216:219], v[212:215], v[16:31]
	global_load_dwordx4 v[114:117], v[146:147], off offset:3712
	global_load_dwordx4 v[130:133], v[156:157], off offset:3712
	v_mfma_f32_32x32x16_bf16 v[0:15], v[216:219], v[252:255], v[0:15]
	global_load_dwordx4 v[134:137], v[158:159], off offset:3712
	global_load_dwordx4 v[138:141], v[160:161], off offset:3712
	s_setprio 0
	s_waitcnt lgkmcnt(0)
	s_barrier
	s_setprio 1
	ds_read_b128 v[212:215], v96 offset:55296
	ds_read_b128 v[216:219], v210 offset:18432
	ds_read_b128 v[220:223], v210 offset:23040
	ds_read_b128 v[224:227], v96 offset:59904
	ds_read_b128 v[228:231], v96 offset:55328
	ds_read_b128 v[244:247], v210 offset:18464
	ds_read_b128 v[252:255], v210 offset:23072
	s_waitcnt lgkmcnt(5)
	v_mfma_f32_32x32x16_bf16 v[48:63], v[212:215], v[216:219], v[48:63]
	s_waitcnt lgkmcnt(4)
	v_mfma_f32_32x32x16_bf16 v[32:47], v[212:215], v[220:223], v[32:47]
	ds_read_b128 v[212:215], v96 offset:59936
	s_waitcnt lgkmcnt(4)
	v_mfma_f32_32x32x16_bf16 v[16:31], v[224:227], v[216:219], v[16:31]
	ds_read_b128 v[216:219], v96 offset:55360
	v_mfma_f32_32x32x16_bf16 v[0:15], v[224:227], v[220:223], v[0:15]
	ds_read_b128 v[224:227], v210 offset:18496
	ds_read_b128 v[220:223], v210 offset:23104
	s_waitcnt lgkmcnt(5)
	v_mfma_f32_32x32x16_bf16 v[48:63], v[228:231], v[244:247], v[48:63]
	s_waitcnt lgkmcnt(4)
	v_mfma_f32_32x32x16_bf16 v[32:47], v[228:231], v[252:255], v[32:47]
	ds_read_b128 v[228:231], v96 offset:59968
	s_waitcnt lgkmcnt(4)
	v_mfma_f32_32x32x16_bf16 v[16:31], v[212:215], v[244:247], v[16:31]
	ds_read_b128 v[244:247], v96 offset:55392
	v_mfma_f32_32x32x16_bf16 v[0:15], v[212:215], v[252:255], v[0:15]
	ds_read_b128 v[212:215], v210 offset:18528
	ds_read_b128 v[252:255], v210 offset:23136
	s_waitcnt lgkmcnt(5)
	v_mfma_f32_32x32x16_bf16 v[48:63], v[216:219], v[224:227], v[48:63]
	s_waitcnt vmcnt(15)
	ds_write_b128 v209, v[64:67]
	global_load_dwordx4 v[98:101], v[148:149], off offset:3840
	s_waitcnt lgkmcnt(5)
	v_mfma_f32_32x32x16_bf16 v[32:47], v[216:219], v[220:223], v[32:47]
	ds_read_b128 v[216:219], v96 offset:60000
	s_waitcnt vmcnt(15)
	ds_write_b128 v209, v[72:75] offset:4608
	s_waitcnt vmcnt(14)
	ds_write_b128 v209, v[76:79] offset:9216
	s_waitcnt lgkmcnt(7)
	v_mfma_f32_32x32x16_bf16 v[16:31], v[228:231], v[224:227], v[16:31]
	s_waitcnt vmcnt(13)
	ds_write_b128 v209, v[80:83] offset:13824
	s_waitcnt vmcnt(12)
	ds_write_b128 v209, v[102:105] offset:36864
	v_mfma_f32_32x32x16_bf16 v[0:15], v[228:231], v[220:223], v[0:15]
	global_load_dwordx4 v[102:105], v[150:151], off offset:3840
	global_load_dwordx4 v[106:109], v[152:153], off offset:3840
	s_waitcnt lgkmcnt(7)
	v_mfma_f32_32x32x16_bf16 v[48:63], v[244:247], v[212:215], v[48:63]
	global_load_dwordx4 v[110:113], v[154:155], off offset:3840
	s_waitcnt vmcnt(14)
	ds_write_b128 v209, v[118:121] offset:41472
	s_waitcnt lgkmcnt(7)
	v_mfma_f32_32x32x16_bf16 v[32:47], v[244:247], v[252:255], v[32:47]
	global_load_dwordx4 v[118:121], v[146:147], off offset:3840
	s_waitcnt vmcnt(14)
	ds_write_b128 v209, v[122:125] offset:46080
	s_waitcnt lgkmcnt(6)
	v_mfma_f32_32x32x16_bf16 v[16:31], v[216:219], v[212:215], v[16:31]
	global_load_dwordx4 v[122:125], v[156:157], off offset:3840
	s_waitcnt vmcnt(14)
	ds_write_b128 v209, v[126:129] offset:50688
	v_mfma_f32_32x32x16_bf16 v[0:15], v[216:219], v[252:255], v[0:15]
	global_load_dwordx4 v[126:129], v[158:159], off offset:3840
	global_load_dwordx4 v[142:145], v[160:161], off offset:3840
	s_setprio 0
	s_waitcnt lgkmcnt(0)
	s_barrier
	s_setprio 1
	ds_read_b128 v[212:215], v96 offset:36864
	ds_read_b128 v[216:219], v210
	ds_read_b128 v[220:223], v210 offset:4608
	ds_read_b128 v[224:227], v96 offset:41472
	ds_read_b128 v[228:231], v96 offset:36896
	ds_read_b128 v[244:247], v210 offset:32
	ds_read_b128 v[252:255], v210 offset:4640
	s_waitcnt lgkmcnt(5)
	v_mfma_f32_32x32x16_bf16 v[48:63], v[212:215], v[216:219], v[48:63]
	s_waitcnt lgkmcnt(4)
	v_mfma_f32_32x32x16_bf16 v[32:47], v[212:215], v[220:223], v[32:47]
	ds_read_b128 v[212:215], v96 offset:41504
	s_waitcnt lgkmcnt(4)
	v_mfma_f32_32x32x16_bf16 v[16:31], v[224:227], v[216:219], v[16:31]
	ds_read_b128 v[216:219], v96 offset:36928
	v_mfma_f32_32x32x16_bf16 v[0:15], v[224:227], v[220:223], v[0:15]
	ds_read_b128 v[224:227], v210 offset:64
	ds_read_b128 v[220:223], v210 offset:4672
	s_waitcnt lgkmcnt(5)
	v_mfma_f32_32x32x16_bf16 v[48:63], v[228:231], v[244:247], v[48:63]
	s_waitcnt lgkmcnt(4)
	v_mfma_f32_32x32x16_bf16 v[32:47], v[228:231], v[252:255], v[32:47]
	ds_read_b128 v[228:231], v96 offset:41536
	s_waitcnt lgkmcnt(4)
	v_mfma_f32_32x32x16_bf16 v[16:31], v[212:215], v[244:247], v[16:31]
	ds_read_b128 v[244:247], v96 offset:36960
	v_mfma_f32_32x32x16_bf16 v[0:15], v[212:215], v[252:255], v[0:15]
	ds_read_b128 v[212:215], v210 offset:96
	ds_read_b128 v[252:255], v210 offset:4704
	s_waitcnt lgkmcnt(5)
	v_mfma_f32_32x32x16_bf16 v[48:63], v[216:219], v[224:227], v[48:63]
	s_waitcnt vmcnt(15)
	ds_write_b128 v209, v[68:71] offset:18432
	global_load_dwordx4 v[64:67], v[148:149], off offset:3968
	s_waitcnt lgkmcnt(5)
	v_mfma_f32_32x32x16_bf16 v[32:47], v[216:219], v[220:223], v[32:47]
	ds_read_b128 v[216:219], v96 offset:41568
	s_waitcnt vmcnt(15)
	ds_write_b128 v209, v[84:87] offset:23040
	global_load_dwordx4 v[68:71], v[150:151], off offset:3968
	s_waitcnt lgkmcnt(6)
	v_mfma_f32_32x32x16_bf16 v[16:31], v[228:231], v[224:227], v[16:31]
	s_waitcnt vmcnt(15)
	ds_write_b128 v209, v[88:91] offset:27648
	global_load_dwordx4 v[72:75], v[152:153], off offset:3968
	v_mfma_f32_32x32x16_bf16 v[0:15], v[228:231], v[220:223], v[0:15]
	s_waitcnt vmcnt(15)
	ds_write_b128 v209, v[92:95] offset:32256
	global_load_dwordx4 v[76:79], v[154:155], off offset:3968
	s_waitcnt lgkmcnt(6)
	v_mfma_f32_32x32x16_bf16 v[48:63], v[244:247], v[212:215], v[48:63]
	s_waitcnt vmcnt(15)
	ds_write_b128 v209, v[114:117] offset:55296
	global_load_dwordx4 v[80:83], v[146:147], off offset:3968
	s_waitcnt lgkmcnt(6)
	v_mfma_f32_32x32x16_bf16 v[32:47], v[244:247], v[252:255], v[32:47]
	s_waitcnt vmcnt(15)
	ds_write_b128 v209, v[130:133] offset:59904
	global_load_dwordx4 v[84:87], v[156:157], off offset:3968
	s_waitcnt lgkmcnt(5)
	v_mfma_f32_32x32x16_bf16 v[16:31], v[216:219], v[212:215], v[16:31]
	s_waitcnt vmcnt(15)
	ds_write_b128 v209, v[134:137] offset:64512
	global_load_dwordx4 v[88:91], v[158:159], off offset:3968
	v_mfma_f32_32x32x16_bf16 v[0:15], v[216:219], v[252:255], v[0:15]
	s_waitcnt vmcnt(15)
	ds_write_b128 v211, v[138:141] offset:13824
	global_load_dwordx4 v[92:95], v[160:161], off offset:3968
	s_setprio 0
	s_waitcnt lgkmcnt(0)
	s_barrier
	s_setprio 1
	ds_read_b128 v[212:215], v96 offset:55296
	ds_read_b128 v[216:219], v210 offset:18432
	ds_read_b128 v[220:223], v210 offset:23040
	ds_read_b128 v[224:227], v96 offset:59904
	ds_read_b128 v[228:231], v96 offset:55328
	ds_read_b128 v[244:247], v210 offset:18464
	ds_read_b128 v[252:255], v210 offset:23072
	s_waitcnt lgkmcnt(5)
	v_mfma_f32_32x32x16_bf16 v[48:63], v[212:215], v[216:219], v[48:63]
	s_waitcnt lgkmcnt(4)
	v_mfma_f32_32x32x16_bf16 v[32:47], v[212:215], v[220:223], v[32:47]
	ds_read_b128 v[212:215], v96 offset:59936
	s_waitcnt lgkmcnt(4)
	v_mfma_f32_32x32x16_bf16 v[16:31], v[224:227], v[216:219], v[16:31]
	ds_read_b128 v[216:219], v96 offset:55360
	v_mfma_f32_32x32x16_bf16 v[0:15], v[224:227], v[220:223], v[0:15]
	ds_read_b128 v[224:227], v210 offset:18496
	ds_read_b128 v[220:223], v210 offset:23104
	s_waitcnt lgkmcnt(5)
	v_mfma_f32_32x32x16_bf16 v[48:63], v[228:231], v[244:247], v[48:63]
	s_waitcnt lgkmcnt(4)
	v_mfma_f32_32x32x16_bf16 v[32:47], v[228:231], v[252:255], v[32:47]
	ds_read_b128 v[228:231], v96 offset:59968
	s_waitcnt lgkmcnt(4)
	v_mfma_f32_32x32x16_bf16 v[16:31], v[212:215], v[244:247], v[16:31]
	ds_read_b128 v[244:247], v96 offset:55392
	v_mfma_f32_32x32x16_bf16 v[0:15], v[212:215], v[252:255], v[0:15]
	ds_read_b128 v[212:215], v210 offset:18528
	ds_read_b128 v[252:255], v210 offset:23136
	s_waitcnt lgkmcnt(5)
	v_mfma_f32_32x32x16_bf16 v[48:63], v[216:219], v[224:227], v[48:63]
	s_movk_i32 s6, 0x1000
	v_add_co_u32_e32 v174, vcc, s6, v148
	s_waitcnt vmcnt(15)
	ds_write_b128 v209, v[98:101]
	s_waitcnt vmcnt(14)
	ds_write_b128 v209, v[102:105] offset:4608
	s_waitcnt lgkmcnt(6)
	v_mfma_f32_32x32x16_bf16 v[32:47], v[216:219], v[220:223], v[32:47]
	ds_read_b128 v[216:219], v96 offset:60000
	s_waitcnt vmcnt(13)
	ds_write_b128 v209, v[106:109] offset:9216
	s_waitcnt vmcnt(12)
	ds_write_b128 v209, v[110:113] offset:13824
	s_waitcnt vmcnt(11)
	ds_write_b128 v209, v[118:121] offset:36864
	s_waitcnt lgkmcnt(9)
	v_mfma_f32_32x32x16_bf16 v[16:31], v[228:231], v[224:227], v[16:31]
	s_waitcnt vmcnt(10)
	ds_write_b128 v209, v[122:125] offset:41472
	s_waitcnt vmcnt(9)
	ds_write_b128 v209, v[126:129] offset:46080
	v_mfma_f32_32x32x16_bf16 v[0:15], v[228:231], v[220:223], v[0:15]
	s_waitcnt vmcnt(8)
	ds_write_b128 v209, v[142:145] offset:50688
	v_addc_co_u32_e32 v175, vcc, 0, v149, vcc
	v_add_co_u32_e32 v176, vcc, s22, v148
	global_load_dwordx4 v[98:101], v[174:175], off
	s_nop 0
	s_waitcnt lgkmcnt(10)
	v_mfma_f32_32x32x16_bf16 v[48:63], v[244:247], v[212:215], v[48:63]
	v_addc_co_u32_e32 v177, vcc, 0, v149, vcc
	v_add_co_u32_e32 v178, vcc, s23, v148
	global_load_dwordx4 v[102:105], v[176:177], off
	s_nop 0
	v_addc_co_u32_e32 v179, vcc, 0, v149, vcc
	v_add_co_u32_e32 v180, vcc, s25, v148
	global_load_dwordx4 v[106:109], v[178:179], off
	s_waitcnt lgkmcnt(9)
	v_mfma_f32_32x32x16_bf16 v[32:47], v[244:247], v[252:255], v[32:47]
	s_nop 0
	v_addc_co_u32_e32 v181, vcc, 0, v149, vcc
	v_add_co_u32_e32 v182, vcc, s6, v146
	global_load_dwordx4 v[110:113], v[180:181], off
	s_nop 0
	v_addc_co_u32_e32 v183, vcc, 0, v147, vcc
	v_add_co_u32_e32 v184, vcc, s22, v146
	s_waitcnt lgkmcnt(6)
	v_mfma_f32_32x32x16_bf16 v[16:31], v[216:219], v[212:215], v[16:31]
	global_load_dwordx4 v[114:117], v[182:183], off
	s_nop 0
	v_addc_co_u32_e32 v185, vcc, 0, v147, vcc
	v_add_co_u32_e32 v186, vcc, s23, v146
	global_load_dwordx4 v[118:121], v[184:185], off
	s_nop 0
	v_mfma_f32_32x32x16_bf16 v[0:15], v[216:219], v[252:255], v[0:15]
	v_addc_co_u32_e32 v187, vcc, 0, v147, vcc
	v_add_co_u32_e32 v188, vcc, s25, v146
	global_load_dwordx4 v[122:125], v[186:187], off
	s_nop 0
	v_addc_co_u32_e32 v189, vcc, 0, v147, vcc
	global_load_dwordx4 v[126:129], v[188:189], off
	s_setprio 0
	s_waitcnt lgkmcnt(0)
	s_barrier
	s_setprio 1
	ds_read_b128 v[212:215], v96 offset:36864
	ds_read_b128 v[216:219], v210
	ds_read_b128 v[220:223], v210 offset:4608
	ds_read_b128 v[224:227], v96 offset:41472
	ds_read_b128 v[228:231], v96 offset:36896
	ds_read_b128 v[244:247], v210 offset:32
	ds_read_b128 v[252:255], v210 offset:4640
	s_waitcnt lgkmcnt(5)
	v_mfma_f32_32x32x16_bf16 v[48:63], v[212:215], v[216:219], v[48:63]
	s_waitcnt lgkmcnt(4)
	v_mfma_f32_32x32x16_bf16 v[32:47], v[212:215], v[220:223], v[32:47]
	ds_read_b128 v[212:215], v96 offset:41504
	s_waitcnt lgkmcnt(4)
	v_mfma_f32_32x32x16_bf16 v[16:31], v[224:227], v[216:219], v[16:31]
	ds_read_b128 v[216:219], v96 offset:36928
	v_mfma_f32_32x32x16_bf16 v[0:15], v[224:227], v[220:223], v[0:15]
	ds_read_b128 v[224:227], v210 offset:64
	ds_read_b128 v[220:223], v210 offset:4672
	s_waitcnt lgkmcnt(5)
	v_mfma_f32_32x32x16_bf16 v[48:63], v[228:231], v[244:247], v[48:63]
	s_waitcnt lgkmcnt(4)
	v_mfma_f32_32x32x16_bf16 v[32:47], v[228:231], v[252:255], v[32:47]
	ds_read_b128 v[228:231], v96 offset:41536
	s_waitcnt lgkmcnt(4)
	v_mfma_f32_32x32x16_bf16 v[16:31], v[212:215], v[244:247], v[16:31]
	ds_read_b128 v[244:247], v96 offset:36960
	v_mfma_f32_32x32x16_bf16 v[0:15], v[212:215], v[252:255], v[0:15]
	ds_read_b128 v[212:215], v210 offset:96
	ds_read_b128 v[252:255], v210 offset:4704
	s_waitcnt lgkmcnt(5)
	v_mfma_f32_32x32x16_bf16 v[48:63], v[216:219], v[224:227], v[48:63]
	s_waitcnt vmcnt(15)
	ds_write_b128 v209, v[64:67] offset:18432
	global_load_dwordx4 v[64:67], v[174:175], off offset:128
	s_waitcnt lgkmcnt(5)
	v_mfma_f32_32x32x16_bf16 v[32:47], v[216:219], v[220:223], v[32:47]
	ds_read_b128 v[216:219], v96 offset:41568
	s_waitcnt vmcnt(15)
	ds_write_b128 v209, v[68:71] offset:23040
	global_load_dwordx4 v[68:71], v[176:177], off offset:128
	s_waitcnt lgkmcnt(6)
	v_mfma_f32_32x32x16_bf16 v[16:31], v[228:231], v[224:227], v[16:31]
	s_waitcnt vmcnt(15)
	ds_write_b128 v209, v[72:75] offset:27648
	global_load_dwordx4 v[72:75], v[178:179], off offset:128
	v_mfma_f32_32x32x16_bf16 v[0:15], v[228:231], v[220:223], v[0:15]
	s_waitcnt vmcnt(15)
	ds_write_b128 v209, v[76:79] offset:32256
	global_load_dwordx4 v[76:79], v[180:181], off offset:128
	s_waitcnt lgkmcnt(6)
	v_mfma_f32_32x32x16_bf16 v[48:63], v[244:247], v[212:215], v[48:63]
	s_waitcnt vmcnt(15)
	ds_write_b128 v209, v[80:83] offset:55296
	global_load_dwordx4 v[80:83], v[182:183], off offset:128
	s_waitcnt lgkmcnt(6)
	v_mfma_f32_32x32x16_bf16 v[32:47], v[244:247], v[252:255], v[32:47]
	s_waitcnt vmcnt(15)
	ds_write_b128 v209, v[84:87] offset:59904
	global_load_dwordx4 v[84:87], v[184:185], off offset:128
	s_waitcnt lgkmcnt(5)
	v_mfma_f32_32x32x16_bf16 v[16:31], v[216:219], v[212:215], v[16:31]
	s_waitcnt vmcnt(15)
	ds_write_b128 v209, v[88:91] offset:64512
	global_load_dwordx4 v[88:91], v[186:187], off offset:128
	v_mfma_f32_32x32x16_bf16 v[0:15], v[216:219], v[252:255], v[0:15]
	s_waitcnt vmcnt(15)
	ds_write_b128 v211, v[92:95] offset:13824
	global_load_dwordx4 v[92:95], v[188:189], off offset:128
	s_setprio 0
	s_waitcnt lgkmcnt(0)
	s_barrier
	s_setprio 1
	ds_read_b128 v[212:215], v96 offset:55296
	ds_read_b128 v[216:219], v210 offset:18432
	ds_read_b128 v[220:223], v210 offset:23040
	ds_read_b128 v[224:227], v96 offset:59904
	ds_read_b128 v[228:231], v96 offset:55328
	ds_read_b128 v[244:247], v210 offset:18464
	ds_read_b128 v[252:255], v210 offset:23072
	s_waitcnt lgkmcnt(5)
	v_mfma_f32_32x32x16_bf16 v[48:63], v[212:215], v[216:219], v[48:63]
	s_waitcnt lgkmcnt(4)
	v_mfma_f32_32x32x16_bf16 v[32:47], v[212:215], v[220:223], v[32:47]
	ds_read_b128 v[212:215], v96 offset:59936
	s_waitcnt lgkmcnt(4)
	v_mfma_f32_32x32x16_bf16 v[16:31], v[224:227], v[216:219], v[16:31]
	ds_read_b128 v[216:219], v96 offset:55360
	v_mfma_f32_32x32x16_bf16 v[0:15], v[224:227], v[220:223], v[0:15]
	ds_read_b128 v[224:227], v210 offset:18496
	ds_read_b128 v[220:223], v210 offset:23104
	s_waitcnt lgkmcnt(5)
	v_mfma_f32_32x32x16_bf16 v[48:63], v[228:231], v[244:247], v[48:63]
	s_waitcnt lgkmcnt(4)
	v_mfma_f32_32x32x16_bf16 v[32:47], v[228:231], v[252:255], v[32:47]
	ds_read_b128 v[228:231], v96 offset:59968
	s_waitcnt lgkmcnt(4)
	v_mfma_f32_32x32x16_bf16 v[16:31], v[212:215], v[244:247], v[16:31]
	ds_read_b128 v[244:247], v96 offset:55392
	v_mfma_f32_32x32x16_bf16 v[0:15], v[212:215], v[252:255], v[0:15]
	ds_read_b128 v[212:215], v210 offset:18528
	ds_read_b128 v[252:255], v210 offset:23136
	s_waitcnt lgkmcnt(5)
	v_mfma_f32_32x32x16_bf16 v[48:63], v[216:219], v[224:227], v[48:63]
	s_waitcnt vmcnt(15)
	ds_write_b128 v209, v[98:101]
	global_load_dwordx4 v[98:101], v[174:175], off offset:256
	s_waitcnt lgkmcnt(5)
	v_mfma_f32_32x32x16_bf16 v[32:47], v[216:219], v[220:223], v[32:47]
	ds_read_b128 v[216:219], v96 offset:60000
	s_waitcnt vmcnt(15)
	ds_write_b128 v209, v[102:105] offset:4608
	global_load_dwordx4 v[102:105], v[176:177], off offset:256
	s_waitcnt lgkmcnt(6)
	v_mfma_f32_32x32x16_bf16 v[16:31], v[228:231], v[224:227], v[16:31]
	s_waitcnt vmcnt(15)
	ds_write_b128 v209, v[106:109] offset:9216
	global_load_dwordx4 v[106:109], v[178:179], off offset:256
	v_mfma_f32_32x32x16_bf16 v[0:15], v[228:231], v[220:223], v[0:15]
	s_waitcnt vmcnt(15)
	ds_write_b128 v209, v[110:113] offset:13824
	global_load_dwordx4 v[110:113], v[180:181], off offset:256
	s_waitcnt lgkmcnt(6)
	v_mfma_f32_32x32x16_bf16 v[48:63], v[244:247], v[212:215], v[48:63]
	s_waitcnt vmcnt(15)
	ds_write_b128 v209, v[114:117] offset:36864
	global_load_dwordx4 v[114:117], v[182:183], off offset:256
	s_waitcnt lgkmcnt(6)
	v_mfma_f32_32x32x16_bf16 v[32:47], v[244:247], v[252:255], v[32:47]
	s_waitcnt vmcnt(15)
	ds_write_b128 v209, v[118:121] offset:41472
	global_load_dwordx4 v[118:121], v[184:185], off offset:256
	s_waitcnt lgkmcnt(5)
	v_mfma_f32_32x32x16_bf16 v[16:31], v[216:219], v[212:215], v[16:31]
	s_waitcnt vmcnt(15)
	ds_write_b128 v209, v[122:125] offset:46080
	global_load_dwordx4 v[122:125], v[186:187], off offset:256
	v_mfma_f32_32x32x16_bf16 v[0:15], v[216:219], v[252:255], v[0:15]
	s_waitcnt vmcnt(15)
	ds_write_b128 v209, v[126:129] offset:50688
	global_load_dwordx4 v[126:129], v[188:189], off offset:256
	s_setprio 0
	s_waitcnt lgkmcnt(0)
	s_barrier
	s_setprio 1
	ds_read_b128 v[212:215], v96 offset:36864
	ds_read_b128 v[216:219], v210
	ds_read_b128 v[220:223], v210 offset:4608
	ds_read_b128 v[224:227], v96 offset:41472
	ds_read_b128 v[228:231], v96 offset:36896
	ds_read_b128 v[244:247], v210 offset:32
	ds_read_b128 v[252:255], v210 offset:4640
	s_waitcnt lgkmcnt(5)
	v_mfma_f32_32x32x16_bf16 v[48:63], v[212:215], v[216:219], v[48:63]
	s_waitcnt lgkmcnt(4)
	v_mfma_f32_32x32x16_bf16 v[32:47], v[212:215], v[220:223], v[32:47]
	ds_read_b128 v[212:215], v96 offset:41504
	s_waitcnt lgkmcnt(4)
	v_mfma_f32_32x32x16_bf16 v[16:31], v[224:227], v[216:219], v[16:31]
	ds_read_b128 v[216:219], v96 offset:36928
	v_mfma_f32_32x32x16_bf16 v[0:15], v[224:227], v[220:223], v[0:15]
	ds_read_b128 v[224:227], v210 offset:64
	ds_read_b128 v[220:223], v210 offset:4672
	s_waitcnt lgkmcnt(5)
	v_mfma_f32_32x32x16_bf16 v[48:63], v[228:231], v[244:247], v[48:63]
	s_waitcnt lgkmcnt(4)
	v_mfma_f32_32x32x16_bf16 v[32:47], v[228:231], v[252:255], v[32:47]
	ds_read_b128 v[228:231], v96 offset:41536
	s_waitcnt lgkmcnt(4)
	v_mfma_f32_32x32x16_bf16 v[16:31], v[212:215], v[244:247], v[16:31]
	ds_read_b128 v[244:247], v96 offset:36960
	v_mfma_f32_32x32x16_bf16 v[0:15], v[212:215], v[252:255], v[0:15]
	ds_read_b128 v[212:215], v210 offset:96
	ds_read_b128 v[252:255], v210 offset:4704
	s_waitcnt lgkmcnt(5)
	v_mfma_f32_32x32x16_bf16 v[48:63], v[216:219], v[224:227], v[48:63]
	s_waitcnt vmcnt(15)
	ds_write_b128 v209, v[64:67] offset:18432
	global_load_dwordx4 v[64:67], v[174:175], off offset:384
	s_waitcnt lgkmcnt(5)
	v_mfma_f32_32x32x16_bf16 v[32:47], v[216:219], v[220:223], v[32:47]
	ds_read_b128 v[216:219], v96 offset:41568
	s_waitcnt vmcnt(15)
	ds_write_b128 v209, v[68:71] offset:23040
	global_load_dwordx4 v[68:71], v[176:177], off offset:384
	s_waitcnt lgkmcnt(6)
	v_mfma_f32_32x32x16_bf16 v[16:31], v[228:231], v[224:227], v[16:31]
	s_waitcnt vmcnt(15)
	ds_write_b128 v209, v[72:75] offset:27648
	global_load_dwordx4 v[72:75], v[178:179], off offset:384
	v_mfma_f32_32x32x16_bf16 v[0:15], v[228:231], v[220:223], v[0:15]
	s_waitcnt vmcnt(15)
	ds_write_b128 v209, v[76:79] offset:32256
	global_load_dwordx4 v[76:79], v[180:181], off offset:384
	s_waitcnt lgkmcnt(6)
	v_mfma_f32_32x32x16_bf16 v[48:63], v[244:247], v[212:215], v[48:63]
	s_waitcnt vmcnt(15)
	ds_write_b128 v209, v[80:83] offset:55296
	global_load_dwordx4 v[80:83], v[182:183], off offset:384
	s_waitcnt lgkmcnt(6)
	v_mfma_f32_32x32x16_bf16 v[32:47], v[244:247], v[252:255], v[32:47]
	s_waitcnt vmcnt(15)
	ds_write_b128 v209, v[84:87] offset:59904
	global_load_dwordx4 v[84:87], v[184:185], off offset:384
	s_waitcnt lgkmcnt(5)
	v_mfma_f32_32x32x16_bf16 v[16:31], v[216:219], v[212:215], v[16:31]
	s_waitcnt vmcnt(15)
	ds_write_b128 v209, v[88:91] offset:64512
	global_load_dwordx4 v[88:91], v[186:187], off offset:384
	v_mfma_f32_32x32x16_bf16 v[0:15], v[216:219], v[252:255], v[0:15]
	s_waitcnt vmcnt(15)
	ds_write_b128 v211, v[92:95] offset:13824
	global_load_dwordx4 v[92:95], v[188:189], off offset:384
	s_setprio 0
	s_waitcnt lgkmcnt(0)
	s_barrier
	s_setprio 1
	ds_read_b128 v[212:215], v96 offset:55296
	ds_read_b128 v[216:219], v210 offset:18432
	ds_read_b128 v[220:223], v210 offset:23040
	ds_read_b128 v[224:227], v96 offset:59904
	ds_read_b128 v[228:231], v96 offset:55328
	ds_read_b128 v[244:247], v210 offset:18464
	ds_read_b128 v[252:255], v210 offset:23072
	s_waitcnt lgkmcnt(5)
	v_mfma_f32_32x32x16_bf16 v[48:63], v[212:215], v[216:219], v[48:63]
	s_waitcnt lgkmcnt(4)
	v_mfma_f32_32x32x16_bf16 v[32:47], v[212:215], v[220:223], v[32:47]
	ds_read_b128 v[212:215], v96 offset:59936
	s_waitcnt lgkmcnt(4)
	v_mfma_f32_32x32x16_bf16 v[16:31], v[224:227], v[216:219], v[16:31]
	ds_read_b128 v[216:219], v96 offset:55360
	v_mfma_f32_32x32x16_bf16 v[0:15], v[224:227], v[220:223], v[0:15]
	ds_read_b128 v[224:227], v210 offset:18496
	ds_read_b128 v[220:223], v210 offset:23104
	s_waitcnt lgkmcnt(5)
	v_mfma_f32_32x32x16_bf16 v[48:63], v[228:231], v[244:247], v[48:63]
	s_waitcnt lgkmcnt(4)
	v_mfma_f32_32x32x16_bf16 v[32:47], v[228:231], v[252:255], v[32:47]
	ds_read_b128 v[228:231], v96 offset:59968
	s_waitcnt lgkmcnt(4)
	v_mfma_f32_32x32x16_bf16 v[16:31], v[212:215], v[244:247], v[16:31]
	ds_read_b128 v[244:247], v96 offset:55392
	v_mfma_f32_32x32x16_bf16 v[0:15], v[212:215], v[252:255], v[0:15]
	ds_read_b128 v[212:215], v210 offset:18528
	ds_read_b128 v[252:255], v210 offset:23136
	s_waitcnt lgkmcnt(5)
	v_mfma_f32_32x32x16_bf16 v[48:63], v[216:219], v[224:227], v[48:63]
	s_waitcnt vmcnt(15)
	ds_write_b128 v209, v[98:101]
	global_load_dwordx4 v[98:101], v[174:175], off offset:512
	s_waitcnt lgkmcnt(5)
	v_mfma_f32_32x32x16_bf16 v[32:47], v[216:219], v[220:223], v[32:47]
	ds_read_b128 v[216:219], v96 offset:60000
	s_waitcnt vmcnt(15)
	ds_write_b128 v209, v[102:105] offset:4608
	global_load_dwordx4 v[102:105], v[176:177], off offset:512
	s_waitcnt lgkmcnt(6)
	v_mfma_f32_32x32x16_bf16 v[16:31], v[228:231], v[224:227], v[16:31]
	s_waitcnt vmcnt(15)
	ds_write_b128 v209, v[106:109] offset:9216
	global_load_dwordx4 v[106:109], v[178:179], off offset:512
	v_mfma_f32_32x32x16_bf16 v[0:15], v[228:231], v[220:223], v[0:15]
	s_waitcnt vmcnt(15)
	ds_write_b128 v209, v[110:113] offset:13824
	global_load_dwordx4 v[110:113], v[180:181], off offset:512
	s_waitcnt lgkmcnt(6)
	v_mfma_f32_32x32x16_bf16 v[48:63], v[244:247], v[212:215], v[48:63]
	s_waitcnt vmcnt(15)
	ds_write_b128 v209, v[114:117] offset:36864
	global_load_dwordx4 v[114:117], v[182:183], off offset:512
	s_waitcnt lgkmcnt(6)
	v_mfma_f32_32x32x16_bf16 v[32:47], v[244:247], v[252:255], v[32:47]
	s_waitcnt vmcnt(15)
	ds_write_b128 v209, v[118:121] offset:41472
	global_load_dwordx4 v[118:121], v[184:185], off offset:512
	s_waitcnt lgkmcnt(5)
	v_mfma_f32_32x32x16_bf16 v[16:31], v[216:219], v[212:215], v[16:31]
	s_waitcnt vmcnt(15)
	ds_write_b128 v209, v[122:125] offset:46080
	global_load_dwordx4 v[122:125], v[186:187], off offset:512
	v_mfma_f32_32x32x16_bf16 v[0:15], v[216:219], v[252:255], v[0:15]
	s_waitcnt vmcnt(15)
	ds_write_b128 v209, v[126:129] offset:50688
	global_load_dwordx4 v[126:129], v[188:189], off offset:512
	s_setprio 0
	s_waitcnt lgkmcnt(0)
	s_barrier
	s_setprio 1
	ds_read_b128 v[212:215], v96 offset:36864
	ds_read_b128 v[216:219], v210
	ds_read_b128 v[220:223], v210 offset:4608
	ds_read_b128 v[224:227], v96 offset:41472
	ds_read_b128 v[228:231], v96 offset:36896
	ds_read_b128 v[244:247], v210 offset:32
	ds_read_b128 v[252:255], v210 offset:4640
	s_waitcnt lgkmcnt(5)
	v_mfma_f32_32x32x16_bf16 v[48:63], v[212:215], v[216:219], v[48:63]
	s_waitcnt lgkmcnt(4)
	v_mfma_f32_32x32x16_bf16 v[32:47], v[212:215], v[220:223], v[32:47]
	ds_read_b128 v[212:215], v96 offset:41504
	s_waitcnt lgkmcnt(4)
	v_mfma_f32_32x32x16_bf16 v[16:31], v[224:227], v[216:219], v[16:31]
	ds_read_b128 v[216:219], v96 offset:36928
	v_mfma_f32_32x32x16_bf16 v[0:15], v[224:227], v[220:223], v[0:15]
	ds_read_b128 v[224:227], v210 offset:64
	ds_read_b128 v[220:223], v210 offset:4672
	s_waitcnt lgkmcnt(5)
	v_mfma_f32_32x32x16_bf16 v[48:63], v[228:231], v[244:247], v[48:63]
	s_waitcnt lgkmcnt(4)
	v_mfma_f32_32x32x16_bf16 v[32:47], v[228:231], v[252:255], v[32:47]
	ds_read_b128 v[228:231], v96 offset:41536
	s_waitcnt lgkmcnt(4)
	v_mfma_f32_32x32x16_bf16 v[16:31], v[212:215], v[244:247], v[16:31]
	ds_read_b128 v[244:247], v96 offset:36960
	v_mfma_f32_32x32x16_bf16 v[0:15], v[212:215], v[252:255], v[0:15]
	ds_read_b128 v[212:215], v210 offset:96
	ds_read_b128 v[252:255], v210 offset:4704
	s_waitcnt lgkmcnt(5)
	v_mfma_f32_32x32x16_bf16 v[48:63], v[216:219], v[224:227], v[48:63]
	s_waitcnt vmcnt(15)
	ds_write_b128 v209, v[64:67] offset:18432
	global_load_dwordx4 v[64:67], v[174:175], off offset:640
	s_waitcnt lgkmcnt(5)
	v_mfma_f32_32x32x16_bf16 v[32:47], v[216:219], v[220:223], v[32:47]
	ds_read_b128 v[216:219], v96 offset:41568
	s_waitcnt vmcnt(15)
	ds_write_b128 v209, v[68:71] offset:23040
	global_load_dwordx4 v[68:71], v[176:177], off offset:640
	s_waitcnt lgkmcnt(6)
	v_mfma_f32_32x32x16_bf16 v[16:31], v[228:231], v[224:227], v[16:31]
	s_waitcnt vmcnt(15)
	ds_write_b128 v209, v[72:75] offset:27648
	global_load_dwordx4 v[72:75], v[178:179], off offset:640
	v_mfma_f32_32x32x16_bf16 v[0:15], v[228:231], v[220:223], v[0:15]
	s_waitcnt vmcnt(15)
	ds_write_b128 v209, v[76:79] offset:32256
	global_load_dwordx4 v[76:79], v[180:181], off offset:640
	s_waitcnt lgkmcnt(6)
	v_mfma_f32_32x32x16_bf16 v[48:63], v[244:247], v[212:215], v[48:63]
	s_waitcnt vmcnt(15)
	ds_write_b128 v209, v[80:83] offset:55296
	global_load_dwordx4 v[80:83], v[182:183], off offset:640
	s_waitcnt lgkmcnt(6)
	v_mfma_f32_32x32x16_bf16 v[32:47], v[244:247], v[252:255], v[32:47]
	s_waitcnt vmcnt(15)
	ds_write_b128 v209, v[84:87] offset:59904
	global_load_dwordx4 v[84:87], v[184:185], off offset:640
	s_waitcnt lgkmcnt(5)
	v_mfma_f32_32x32x16_bf16 v[16:31], v[216:219], v[212:215], v[16:31]
	s_waitcnt vmcnt(15)
	ds_write_b128 v209, v[88:91] offset:64512
	global_load_dwordx4 v[88:91], v[186:187], off offset:640
	v_mfma_f32_32x32x16_bf16 v[0:15], v[216:219], v[252:255], v[0:15]
	s_waitcnt vmcnt(15)
	ds_write_b128 v211, v[92:95] offset:13824
	global_load_dwordx4 v[92:95], v[188:189], off offset:640
	s_setprio 0
	s_waitcnt lgkmcnt(0)
	s_barrier
	s_setprio 1
	ds_read_b128 v[212:215], v96 offset:55296
	ds_read_b128 v[216:219], v210 offset:18432
	ds_read_b128 v[220:223], v210 offset:23040
	ds_read_b128 v[224:227], v96 offset:59904
	ds_read_b128 v[228:231], v96 offset:55328
	ds_read_b128 v[244:247], v210 offset:18464
	ds_read_b128 v[252:255], v210 offset:23072
	s_waitcnt lgkmcnt(5)
	v_mfma_f32_32x32x16_bf16 v[48:63], v[212:215], v[216:219], v[48:63]
	s_waitcnt lgkmcnt(4)
	v_mfma_f32_32x32x16_bf16 v[32:47], v[212:215], v[220:223], v[32:47]
	ds_read_b128 v[212:215], v96 offset:59936
	s_waitcnt lgkmcnt(4)
	v_mfma_f32_32x32x16_bf16 v[16:31], v[224:227], v[216:219], v[16:31]
	ds_read_b128 v[216:219], v96 offset:55360
	v_mfma_f32_32x32x16_bf16 v[0:15], v[224:227], v[220:223], v[0:15]
	ds_read_b128 v[224:227], v210 offset:18496
	ds_read_b128 v[220:223], v210 offset:23104
	s_waitcnt lgkmcnt(5)
	v_mfma_f32_32x32x16_bf16 v[48:63], v[228:231], v[244:247], v[48:63]
	s_waitcnt lgkmcnt(4)
	v_mfma_f32_32x32x16_bf16 v[32:47], v[228:231], v[252:255], v[32:47]
	ds_read_b128 v[228:231], v96 offset:59968
	s_waitcnt lgkmcnt(4)
	v_mfma_f32_32x32x16_bf16 v[16:31], v[212:215], v[244:247], v[16:31]
	ds_read_b128 v[244:247], v96 offset:55392
	v_mfma_f32_32x32x16_bf16 v[0:15], v[212:215], v[252:255], v[0:15]
	ds_read_b128 v[212:215], v210 offset:18528
	ds_read_b128 v[252:255], v210 offset:23136
	s_waitcnt lgkmcnt(5)
	v_mfma_f32_32x32x16_bf16 v[48:63], v[216:219], v[224:227], v[48:63]
	s_waitcnt vmcnt(15)
	ds_write_b128 v209, v[98:101]
	global_load_dwordx4 v[98:101], v[174:175], off offset:768
	s_waitcnt lgkmcnt(5)
	v_mfma_f32_32x32x16_bf16 v[32:47], v[216:219], v[220:223], v[32:47]
	ds_read_b128 v[216:219], v96 offset:60000
	s_waitcnt vmcnt(15)
	ds_write_b128 v209, v[102:105] offset:4608
	global_load_dwordx4 v[102:105], v[176:177], off offset:768
	s_waitcnt lgkmcnt(6)
	v_mfma_f32_32x32x16_bf16 v[16:31], v[228:231], v[224:227], v[16:31]
	s_waitcnt vmcnt(15)
	ds_write_b128 v209, v[106:109] offset:9216
	global_load_dwordx4 v[106:109], v[178:179], off offset:768
	v_mfma_f32_32x32x16_bf16 v[0:15], v[228:231], v[220:223], v[0:15]
	s_waitcnt vmcnt(15)
	ds_write_b128 v209, v[110:113] offset:13824
	global_load_dwordx4 v[110:113], v[180:181], off offset:768
	s_waitcnt lgkmcnt(6)
	v_mfma_f32_32x32x16_bf16 v[48:63], v[244:247], v[212:215], v[48:63]
	s_waitcnt vmcnt(15)
	ds_write_b128 v209, v[114:117] offset:36864
	global_load_dwordx4 v[114:117], v[182:183], off offset:768
	s_waitcnt lgkmcnt(6)
	v_mfma_f32_32x32x16_bf16 v[32:47], v[244:247], v[252:255], v[32:47]
	s_waitcnt vmcnt(15)
	ds_write_b128 v209, v[118:121] offset:41472
	global_load_dwordx4 v[118:121], v[184:185], off offset:768
	s_waitcnt lgkmcnt(5)
	v_mfma_f32_32x32x16_bf16 v[16:31], v[216:219], v[212:215], v[16:31]
	s_waitcnt vmcnt(15)
	ds_write_b128 v209, v[122:125] offset:46080
	global_load_dwordx4 v[122:125], v[186:187], off offset:768
	v_mfma_f32_32x32x16_bf16 v[0:15], v[216:219], v[252:255], v[0:15]
	s_waitcnt vmcnt(15)
	ds_write_b128 v209, v[126:129] offset:50688
	global_load_dwordx4 v[126:129], v[188:189], off offset:768
	s_setprio 0
	s_waitcnt lgkmcnt(0)
	s_barrier
	s_setprio 1
	ds_read_b128 v[212:215], v96 offset:36864
	ds_read_b128 v[216:219], v210
	ds_read_b128 v[220:223], v210 offset:4608
	ds_read_b128 v[224:227], v96 offset:41472
	ds_read_b128 v[228:231], v96 offset:36896
	ds_read_b128 v[244:247], v210 offset:32
	ds_read_b128 v[252:255], v210 offset:4640
	s_waitcnt lgkmcnt(5)
	v_mfma_f32_32x32x16_bf16 v[48:63], v[212:215], v[216:219], v[48:63]
	s_waitcnt lgkmcnt(4)
	v_mfma_f32_32x32x16_bf16 v[32:47], v[212:215], v[220:223], v[32:47]
	ds_read_b128 v[212:215], v96 offset:41504
	s_waitcnt lgkmcnt(4)
	v_mfma_f32_32x32x16_bf16 v[16:31], v[224:227], v[216:219], v[16:31]
	ds_read_b128 v[216:219], v96 offset:36928
	v_mfma_f32_32x32x16_bf16 v[0:15], v[224:227], v[220:223], v[0:15]
	ds_read_b128 v[224:227], v210 offset:64
	ds_read_b128 v[220:223], v210 offset:4672
	s_waitcnt lgkmcnt(5)
	v_mfma_f32_32x32x16_bf16 v[48:63], v[228:231], v[244:247], v[48:63]
	s_waitcnt lgkmcnt(4)
	v_mfma_f32_32x32x16_bf16 v[32:47], v[228:231], v[252:255], v[32:47]
	ds_read_b128 v[228:231], v96 offset:41536
	s_waitcnt lgkmcnt(4)
	v_mfma_f32_32x32x16_bf16 v[16:31], v[212:215], v[244:247], v[16:31]
	ds_read_b128 v[244:247], v96 offset:36960
	v_mfma_f32_32x32x16_bf16 v[0:15], v[212:215], v[252:255], v[0:15]
	ds_read_b128 v[212:215], v210 offset:96
	ds_read_b128 v[252:255], v210 offset:4704
	s_waitcnt lgkmcnt(5)
	v_mfma_f32_32x32x16_bf16 v[48:63], v[216:219], v[224:227], v[48:63]
	s_waitcnt vmcnt(15)
	ds_write_b128 v209, v[64:67] offset:18432
	global_load_dwordx4 v[64:67], v[174:175], off offset:896
	s_waitcnt lgkmcnt(5)
	v_mfma_f32_32x32x16_bf16 v[32:47], v[216:219], v[220:223], v[32:47]
	ds_read_b128 v[216:219], v96 offset:41568
	s_waitcnt vmcnt(15)
	ds_write_b128 v209, v[68:71] offset:23040
	global_load_dwordx4 v[68:71], v[176:177], off offset:896
	s_waitcnt lgkmcnt(6)
	v_mfma_f32_32x32x16_bf16 v[16:31], v[228:231], v[224:227], v[16:31]
	s_waitcnt vmcnt(15)
	ds_write_b128 v209, v[72:75] offset:27648
	global_load_dwordx4 v[72:75], v[178:179], off offset:896
	v_mfma_f32_32x32x16_bf16 v[0:15], v[228:231], v[220:223], v[0:15]
	s_waitcnt vmcnt(15)
	ds_write_b128 v209, v[76:79] offset:32256
	global_load_dwordx4 v[76:79], v[180:181], off offset:896
	s_waitcnt lgkmcnt(6)
	v_mfma_f32_32x32x16_bf16 v[48:63], v[244:247], v[212:215], v[48:63]
	s_waitcnt vmcnt(15)
	ds_write_b128 v209, v[80:83] offset:55296
	global_load_dwordx4 v[80:83], v[182:183], off offset:896
	s_waitcnt lgkmcnt(6)
	v_mfma_f32_32x32x16_bf16 v[32:47], v[244:247], v[252:255], v[32:47]
	s_waitcnt vmcnt(15)
	ds_write_b128 v209, v[84:87] offset:59904
	global_load_dwordx4 v[84:87], v[184:185], off offset:896
	s_waitcnt lgkmcnt(5)
	v_mfma_f32_32x32x16_bf16 v[16:31], v[216:219], v[212:215], v[16:31]
	s_waitcnt vmcnt(15)
	ds_write_b128 v209, v[88:91] offset:64512
	global_load_dwordx4 v[88:91], v[186:187], off offset:896
	v_mfma_f32_32x32x16_bf16 v[0:15], v[216:219], v[252:255], v[0:15]
	s_waitcnt vmcnt(15)
	ds_write_b128 v211, v[92:95] offset:13824
	global_load_dwordx4 v[92:95], v[188:189], off offset:896
	s_setprio 0
	s_waitcnt lgkmcnt(0)
	s_barrier
	s_setprio 1
	ds_read_b128 v[212:215], v96 offset:55296
	ds_read_b128 v[216:219], v210 offset:18432
	ds_read_b128 v[220:223], v210 offset:23040
	ds_read_b128 v[224:227], v96 offset:59904
	ds_read_b128 v[228:231], v96 offset:55328
	ds_read_b128 v[244:247], v210 offset:18464
	ds_read_b128 v[252:255], v210 offset:23072
	s_waitcnt lgkmcnt(5)
	v_mfma_f32_32x32x16_bf16 v[48:63], v[212:215], v[216:219], v[48:63]
	s_waitcnt lgkmcnt(4)
	v_mfma_f32_32x32x16_bf16 v[32:47], v[212:215], v[220:223], v[32:47]
	ds_read_b128 v[212:215], v96 offset:59936
	s_waitcnt lgkmcnt(4)
	v_mfma_f32_32x32x16_bf16 v[16:31], v[224:227], v[216:219], v[16:31]
	ds_read_b128 v[216:219], v96 offset:55360
	v_mfma_f32_32x32x16_bf16 v[0:15], v[224:227], v[220:223], v[0:15]
	ds_read_b128 v[224:227], v210 offset:18496
	ds_read_b128 v[220:223], v210 offset:23104
	s_waitcnt lgkmcnt(5)
	v_mfma_f32_32x32x16_bf16 v[48:63], v[228:231], v[244:247], v[48:63]
	s_waitcnt lgkmcnt(4)
	v_mfma_f32_32x32x16_bf16 v[32:47], v[228:231], v[252:255], v[32:47]
	ds_read_b128 v[228:231], v96 offset:59968
	s_waitcnt lgkmcnt(4)
	v_mfma_f32_32x32x16_bf16 v[16:31], v[212:215], v[244:247], v[16:31]
	ds_read_b128 v[244:247], v96 offset:55392
	v_mfma_f32_32x32x16_bf16 v[0:15], v[212:215], v[252:255], v[0:15]
	ds_read_b128 v[212:215], v210 offset:18528
	ds_read_b128 v[252:255], v210 offset:23136
	s_waitcnt lgkmcnt(5)
	v_mfma_f32_32x32x16_bf16 v[48:63], v[216:219], v[224:227], v[48:63]
	s_waitcnt vmcnt(15)
	ds_write_b128 v209, v[98:101]
	global_load_dwordx4 v[98:101], v[174:175], off offset:1024
	s_waitcnt lgkmcnt(5)
	v_mfma_f32_32x32x16_bf16 v[32:47], v[216:219], v[220:223], v[32:47]
	ds_read_b128 v[216:219], v96 offset:60000
	s_waitcnt vmcnt(15)
	ds_write_b128 v209, v[102:105] offset:4608
	global_load_dwordx4 v[102:105], v[176:177], off offset:1024
	s_waitcnt lgkmcnt(6)
	v_mfma_f32_32x32x16_bf16 v[16:31], v[228:231], v[224:227], v[16:31]
	s_waitcnt vmcnt(15)
	ds_write_b128 v209, v[106:109] offset:9216
	global_load_dwordx4 v[106:109], v[178:179], off offset:1024
	v_mfma_f32_32x32x16_bf16 v[0:15], v[228:231], v[220:223], v[0:15]
	s_waitcnt vmcnt(15)
	ds_write_b128 v209, v[110:113] offset:13824
	global_load_dwordx4 v[110:113], v[180:181], off offset:1024
	s_waitcnt lgkmcnt(6)
	v_mfma_f32_32x32x16_bf16 v[48:63], v[244:247], v[212:215], v[48:63]
	s_waitcnt vmcnt(15)
	ds_write_b128 v209, v[114:117] offset:36864
	global_load_dwordx4 v[114:117], v[182:183], off offset:1024
	s_waitcnt lgkmcnt(6)
	v_mfma_f32_32x32x16_bf16 v[32:47], v[244:247], v[252:255], v[32:47]
	s_waitcnt vmcnt(15)
	ds_write_b128 v209, v[118:121] offset:41472
	global_load_dwordx4 v[118:121], v[184:185], off offset:1024
	s_waitcnt lgkmcnt(5)
	v_mfma_f32_32x32x16_bf16 v[16:31], v[216:219], v[212:215], v[16:31]
	s_waitcnt vmcnt(15)
	ds_write_b128 v209, v[122:125] offset:46080
	global_load_dwordx4 v[122:125], v[186:187], off offset:1024
	v_mfma_f32_32x32x16_bf16 v[0:15], v[216:219], v[252:255], v[0:15]
	s_waitcnt vmcnt(15)
	ds_write_b128 v209, v[126:129] offset:50688
	global_load_dwordx4 v[126:129], v[188:189], off offset:1024
	s_setprio 0
	s_waitcnt lgkmcnt(0)
	s_barrier
	s_setprio 1
	ds_read_b128 v[212:215], v96 offset:36864
	ds_read_b128 v[216:219], v210
	ds_read_b128 v[220:223], v210 offset:4608
	ds_read_b128 v[224:227], v96 offset:41472
	ds_read_b128 v[228:231], v96 offset:36896
	ds_read_b128 v[244:247], v210 offset:32
	ds_read_b128 v[252:255], v210 offset:4640
	s_waitcnt lgkmcnt(5)
	v_mfma_f32_32x32x16_bf16 v[48:63], v[212:215], v[216:219], v[48:63]
	s_waitcnt lgkmcnt(4)
	v_mfma_f32_32x32x16_bf16 v[32:47], v[212:215], v[220:223], v[32:47]
	ds_read_b128 v[212:215], v96 offset:41504
	s_waitcnt lgkmcnt(4)
	v_mfma_f32_32x32x16_bf16 v[16:31], v[224:227], v[216:219], v[16:31]
	ds_read_b128 v[216:219], v96 offset:36928
	v_mfma_f32_32x32x16_bf16 v[0:15], v[224:227], v[220:223], v[0:15]
	ds_read_b128 v[224:227], v210 offset:64
	ds_read_b128 v[220:223], v210 offset:4672
	s_waitcnt lgkmcnt(5)
	v_mfma_f32_32x32x16_bf16 v[48:63], v[228:231], v[244:247], v[48:63]
	s_waitcnt lgkmcnt(4)
	v_mfma_f32_32x32x16_bf16 v[32:47], v[228:231], v[252:255], v[32:47]
	ds_read_b128 v[228:231], v96 offset:41536
	s_waitcnt lgkmcnt(4)
	v_mfma_f32_32x32x16_bf16 v[16:31], v[212:215], v[244:247], v[16:31]
	ds_read_b128 v[244:247], v96 offset:36960
	v_mfma_f32_32x32x16_bf16 v[0:15], v[212:215], v[252:255], v[0:15]
	ds_read_b128 v[212:215], v210 offset:96
	ds_read_b128 v[252:255], v210 offset:4704
	s_waitcnt lgkmcnt(5)
	v_mfma_f32_32x32x16_bf16 v[48:63], v[216:219], v[224:227], v[48:63]
	s_waitcnt vmcnt(15)
	ds_write_b128 v209, v[64:67] offset:18432
	global_load_dwordx4 v[130:133], v[174:175], off offset:1152
	s_waitcnt lgkmcnt(5)
	v_mfma_f32_32x32x16_bf16 v[32:47], v[216:219], v[220:223], v[32:47]
	ds_read_b128 v[216:219], v96 offset:41568
	s_waitcnt vmcnt(15)
	ds_write_b128 v209, v[68:71] offset:23040
	global_load_dwordx4 v[134:137], v[176:177], off offset:1152
	s_waitcnt lgkmcnt(6)
	v_mfma_f32_32x32x16_bf16 v[16:31], v[228:231], v[224:227], v[16:31]
	s_waitcnt vmcnt(15)
	ds_write_b128 v209, v[72:75] offset:27648
	global_load_dwordx4 v[138:141], v[178:179], off offset:1152
	v_mfma_f32_32x32x16_bf16 v[0:15], v[228:231], v[220:223], v[0:15]
	s_waitcnt vmcnt(15)
	ds_write_b128 v209, v[76:79] offset:32256
	global_load_dwordx4 v[142:145], v[180:181], off offset:1152
	s_waitcnt lgkmcnt(6)
	v_mfma_f32_32x32x16_bf16 v[48:63], v[244:247], v[212:215], v[48:63]
	s_waitcnt vmcnt(15)
	ds_write_b128 v209, v[80:83] offset:55296
	global_load_dwordx4 v[146:149], v[182:183], off offset:1152
	s_waitcnt lgkmcnt(6)
	v_mfma_f32_32x32x16_bf16 v[32:47], v[244:247], v[252:255], v[32:47]
	s_waitcnt vmcnt(15)
	ds_write_b128 v209, v[84:87] offset:59904
	global_load_dwordx4 v[150:153], v[184:185], off offset:1152
	s_waitcnt lgkmcnt(5)
	v_mfma_f32_32x32x16_bf16 v[16:31], v[216:219], v[212:215], v[16:31]
	s_waitcnt vmcnt(15)
	ds_write_b128 v209, v[88:91] offset:64512
	global_load_dwordx4 v[154:157], v[186:187], off offset:1152
	v_mfma_f32_32x32x16_bf16 v[0:15], v[216:219], v[252:255], v[0:15]
	s_waitcnt vmcnt(15)
	ds_write_b128 v211, v[92:95] offset:13824
	global_load_dwordx4 v[158:161], v[188:189], off offset:1152
	s_setprio 0
	s_waitcnt lgkmcnt(0)
	s_barrier
	s_setprio 1
	ds_read_b128 v[212:215], v96 offset:55296
	ds_read_b128 v[216:219], v210 offset:18432
	ds_read_b128 v[220:223], v210 offset:23040
	ds_read_b128 v[224:227], v96 offset:59904
	ds_read_b128 v[228:231], v96 offset:55328
	ds_read_b128 v[244:247], v210 offset:18464
	ds_read_b128 v[252:255], v210 offset:23072
	s_waitcnt lgkmcnt(5)
	v_mfma_f32_32x32x16_bf16 v[48:63], v[212:215], v[216:219], v[48:63]
	s_waitcnt lgkmcnt(4)
	v_mfma_f32_32x32x16_bf16 v[32:47], v[212:215], v[220:223], v[32:47]
	ds_read_b128 v[212:215], v96 offset:59936
	s_waitcnt lgkmcnt(4)
	v_mfma_f32_32x32x16_bf16 v[16:31], v[224:227], v[216:219], v[16:31]
	ds_read_b128 v[216:219], v96 offset:55360
	v_mfma_f32_32x32x16_bf16 v[0:15], v[224:227], v[220:223], v[0:15]
	ds_read_b128 v[224:227], v210 offset:18496
	ds_read_b128 v[220:223], v210 offset:23104
	s_waitcnt lgkmcnt(5)
	v_mfma_f32_32x32x16_bf16 v[48:63], v[228:231], v[244:247], v[48:63]
	s_waitcnt lgkmcnt(4)
	v_mfma_f32_32x32x16_bf16 v[32:47], v[228:231], v[252:255], v[32:47]
	ds_read_b128 v[228:231], v96 offset:59968
	s_waitcnt lgkmcnt(4)
	v_mfma_f32_32x32x16_bf16 v[16:31], v[212:215], v[244:247], v[16:31]
	ds_read_b128 v[244:247], v96 offset:55392
	v_mfma_f32_32x32x16_bf16 v[0:15], v[212:215], v[252:255], v[0:15]
	ds_read_b128 v[212:215], v210 offset:18528
	ds_read_b128 v[252:255], v210 offset:23136
	s_waitcnt lgkmcnt(5)
	v_mfma_f32_32x32x16_bf16 v[48:63], v[216:219], v[224:227], v[48:63]
	s_waitcnt vmcnt(15)
	ds_write_b128 v209, v[98:101]
	global_load_dwordx4 v[64:67], v[174:175], off offset:1280
	s_waitcnt lgkmcnt(5)
	v_mfma_f32_32x32x16_bf16 v[32:47], v[216:219], v[220:223], v[32:47]
	ds_read_b128 v[216:219], v96 offset:60000
	s_waitcnt vmcnt(15)
	ds_write_b128 v209, v[102:105] offset:4608
	global_load_dwordx4 v[68:71], v[176:177], off offset:1280
	s_waitcnt lgkmcnt(6)
	v_mfma_f32_32x32x16_bf16 v[16:31], v[228:231], v[224:227], v[16:31]
	s_waitcnt vmcnt(15)
	ds_write_b128 v209, v[106:109] offset:9216
	global_load_dwordx4 v[72:75], v[178:179], off offset:1280
	v_mfma_f32_32x32x16_bf16 v[0:15], v[228:231], v[220:223], v[0:15]
	s_waitcnt vmcnt(15)
	ds_write_b128 v209, v[110:113] offset:13824
	global_load_dwordx4 v[76:79], v[180:181], off offset:1280
	s_waitcnt lgkmcnt(6)
	v_mfma_f32_32x32x16_bf16 v[48:63], v[244:247], v[212:215], v[48:63]
	s_waitcnt vmcnt(15)
	ds_write_b128 v209, v[114:117] offset:36864
	global_load_dwordx4 v[80:83], v[182:183], off offset:1280
	s_waitcnt lgkmcnt(6)
	v_mfma_f32_32x32x16_bf16 v[32:47], v[244:247], v[252:255], v[32:47]
	s_waitcnt vmcnt(15)
	ds_write_b128 v209, v[118:121] offset:41472
	global_load_dwordx4 v[84:87], v[184:185], off offset:1280
	s_waitcnt lgkmcnt(5)
	v_mfma_f32_32x32x16_bf16 v[16:31], v[216:219], v[212:215], v[16:31]
	s_waitcnt vmcnt(15)
	ds_write_b128 v209, v[122:125] offset:46080
	global_load_dwordx4 v[88:91], v[186:187], off offset:1280
	v_mfma_f32_32x32x16_bf16 v[0:15], v[216:219], v[252:255], v[0:15]
	s_waitcnt vmcnt(15)
	ds_write_b128 v209, v[126:129] offset:50688
	global_load_dwordx4 v[92:95], v[188:189], off offset:1280
	s_setprio 0
	s_waitcnt lgkmcnt(0)
	s_barrier
	s_setprio 1
	ds_read_b128 v[212:215], v96 offset:36864
	ds_read_b128 v[216:219], v210
	ds_read_b128 v[220:223], v210 offset:4608
	ds_read_b128 v[224:227], v96 offset:41472
	ds_read_b128 v[228:231], v96 offset:36896
	ds_read_b128 v[244:247], v210 offset:32
	ds_read_b128 v[252:255], v210 offset:4640
	s_waitcnt lgkmcnt(5)
	v_mfma_f32_32x32x16_bf16 v[48:63], v[212:215], v[216:219], v[48:63]
	s_waitcnt lgkmcnt(4)
	v_mfma_f32_32x32x16_bf16 v[32:47], v[212:215], v[220:223], v[32:47]
	ds_read_b128 v[212:215], v96 offset:41504
	s_waitcnt lgkmcnt(4)
	v_mfma_f32_32x32x16_bf16 v[16:31], v[224:227], v[216:219], v[16:31]
	ds_read_b128 v[216:219], v96 offset:36928
	v_mfma_f32_32x32x16_bf16 v[0:15], v[224:227], v[220:223], v[0:15]
	ds_read_b128 v[224:227], v210 offset:64
	ds_read_b128 v[220:223], v210 offset:4672
	s_waitcnt lgkmcnt(5)
	v_mfma_f32_32x32x16_bf16 v[48:63], v[228:231], v[244:247], v[48:63]
	s_waitcnt lgkmcnt(4)
	v_mfma_f32_32x32x16_bf16 v[32:47], v[228:231], v[252:255], v[32:47]
	ds_read_b128 v[228:231], v96 offset:41536
	s_waitcnt lgkmcnt(4)
	v_mfma_f32_32x32x16_bf16 v[16:31], v[212:215], v[244:247], v[16:31]
	ds_read_b128 v[244:247], v96 offset:36960
	v_mfma_f32_32x32x16_bf16 v[0:15], v[212:215], v[252:255], v[0:15]
	ds_read_b128 v[212:215], v210 offset:96
	ds_read_b128 v[252:255], v210 offset:4704
	s_waitcnt lgkmcnt(5)
	v_mfma_f32_32x32x16_bf16 v[48:63], v[216:219], v[224:227], v[48:63]
	s_waitcnt vmcnt(15)
	ds_write_b128 v209, v[130:133] offset:18432
	global_load_dwordx4 v[100:103], v[174:175], off offset:1408
	s_waitcnt lgkmcnt(5)
	v_mfma_f32_32x32x16_bf16 v[32:47], v[216:219], v[220:223], v[32:47]
	ds_read_b128 v[216:219], v96 offset:41568
	s_waitcnt vmcnt(15)
	ds_write_b128 v209, v[134:137] offset:23040
	global_load_dwordx4 v[104:107], v[176:177], off offset:1408
	s_waitcnt lgkmcnt(6)
	v_mfma_f32_32x32x16_bf16 v[16:31], v[228:231], v[224:227], v[16:31]
	s_waitcnt vmcnt(15)
	ds_write_b128 v209, v[138:141] offset:27648
	global_load_dwordx4 v[108:111], v[178:179], off offset:1408
	v_mfma_f32_32x32x16_bf16 v[0:15], v[228:231], v[220:223], v[0:15]
	s_waitcnt vmcnt(15)
	ds_write_b128 v209, v[142:145] offset:32256
	global_load_dwordx4 v[116:119], v[180:181], off offset:1408
	s_waitcnt lgkmcnt(6)
	v_mfma_f32_32x32x16_bf16 v[48:63], v[244:247], v[212:215], v[48:63]
	s_waitcnt vmcnt(15)
	ds_write_b128 v209, v[146:149] offset:55296
	global_load_dwordx4 v[112:115], v[182:183], off offset:1408
	s_waitcnt lgkmcnt(6)
	v_mfma_f32_32x32x16_bf16 v[32:47], v[244:247], v[252:255], v[32:47]
	s_waitcnt vmcnt(15)
	ds_write_b128 v209, v[150:153] offset:59904
	global_load_dwordx4 v[120:123], v[184:185], off offset:1408
	s_waitcnt lgkmcnt(5)
	v_mfma_f32_32x32x16_bf16 v[16:31], v[216:219], v[212:215], v[16:31]
	s_waitcnt vmcnt(15)
	ds_write_b128 v209, v[154:157] offset:64512
	global_load_dwordx4 v[124:127], v[186:187], off offset:1408
	v_mfma_f32_32x32x16_bf16 v[0:15], v[216:219], v[252:255], v[0:15]
	s_waitcnt vmcnt(15)
	ds_write_b128 v211, v[158:161] offset:13824
	global_load_dwordx4 v[128:131], v[188:189], off offset:1408
	s_setprio 0
	s_waitcnt lgkmcnt(0)
	s_barrier
	s_setprio 1
	ds_read_b128 v[212:215], v96 offset:55296
	ds_read_b128 v[216:219], v210 offset:18432
	ds_read_b128 v[220:223], v210 offset:23040
	ds_read_b128 v[224:227], v96 offset:59904
	ds_read_b128 v[228:231], v96 offset:55328
	ds_read_b128 v[244:247], v210 offset:18464
	ds_read_b128 v[252:255], v210 offset:23072
	s_waitcnt lgkmcnt(5)
	v_mfma_f32_32x32x16_bf16 v[48:63], v[212:215], v[216:219], v[48:63]
	s_waitcnt lgkmcnt(4)
	v_mfma_f32_32x32x16_bf16 v[32:47], v[212:215], v[220:223], v[32:47]
	ds_read_b128 v[212:215], v96 offset:59936
	s_waitcnt lgkmcnt(4)
	v_mfma_f32_32x32x16_bf16 v[16:31], v[224:227], v[216:219], v[16:31]
	ds_read_b128 v[216:219], v96 offset:55360
	v_mfma_f32_32x32x16_bf16 v[0:15], v[224:227], v[220:223], v[0:15]
	ds_read_b128 v[224:227], v210 offset:18496
	ds_read_b128 v[220:223], v210 offset:23104
	s_waitcnt lgkmcnt(5)
	v_mfma_f32_32x32x16_bf16 v[48:63], v[228:231], v[244:247], v[48:63]
	s_waitcnt lgkmcnt(4)
	v_mfma_f32_32x32x16_bf16 v[32:47], v[228:231], v[252:255], v[32:47]
	ds_read_b128 v[228:231], v96 offset:59968
	s_waitcnt lgkmcnt(4)
	v_mfma_f32_32x32x16_bf16 v[16:31], v[212:215], v[244:247], v[16:31]
	ds_read_b128 v[244:247], v96 offset:55392
	v_mfma_f32_32x32x16_bf16 v[0:15], v[212:215], v[252:255], v[0:15]
	ds_read_b128 v[212:215], v210 offset:18528
	ds_read_b128 v[252:255], v210 offset:23136
	s_waitcnt lgkmcnt(5)
	v_mfma_f32_32x32x16_bf16 v[48:63], v[216:219], v[224:227], v[48:63]
	s_waitcnt lgkmcnt(4)
	v_mfma_f32_32x32x16_bf16 v[32:47], v[216:219], v[220:223], v[32:47]
	ds_read_b128 v[216:219], v96 offset:60000
	s_waitcnt lgkmcnt(4)
	v_mfma_f32_32x32x16_bf16 v[16:31], v[228:231], v[224:227], v[16:31]
	v_mfma_f32_32x32x16_bf16 v[0:15], v[228:231], v[220:223], v[0:15]
	s_waitcnt lgkmcnt(2)
	v_mfma_f32_32x32x16_bf16 v[48:63], v[244:247], v[212:215], v[48:63]
	s_waitcnt lgkmcnt(1)
	v_mfma_f32_32x32x16_bf16 v[32:47], v[244:247], v[252:255], v[32:47]
	s_waitcnt lgkmcnt(0)
	v_mfma_f32_32x32x16_bf16 v[16:31], v[216:219], v[212:215], v[16:31]
	v_mfma_f32_32x32x16_bf16 v[0:15], v[216:219], v[252:255], v[0:15]
	s_setprio 0
	v_cndmask_b32_e64 v98, 0, 1, s[44:45]
	v_cmp_ne_u32_e64 s[38:39], 1, v98
	s_andn2_b64 vcc, exec, s[44:45]
	s_waitcnt vmcnt(15)
	ds_write_b128 v209, v[64:67]
	s_waitcnt vmcnt(14)
	ds_write_b128 v209, v[68:71] offset:4608
	s_waitcnt vmcnt(13)
	ds_write_b128 v209, v[72:75] offset:9216
	s_waitcnt vmcnt(12)
	ds_write_b128 v209, v[76:79] offset:13824
	s_waitcnt vmcnt(11)
	ds_write_b128 v209, v[80:83] offset:36864
	s_waitcnt vmcnt(10)
	ds_write_b128 v209, v[84:87] offset:41472
	s_waitcnt vmcnt(9)
	ds_write_b128 v209, v[88:91] offset:46080
	s_waitcnt vmcnt(8)
	ds_write_b128 v209, v[92:95] offset:50688
	s_cbranch_vccnz .LBB0_1418
	v_add_co_u32_e32 v68, vcc, 0x2c000, v172
	global_load_dwordx4 v[64:67], v[172:173], off
	s_nop 0
	v_addc_co_u32_e32 v69, vcc, 0, v173, vcc
	v_add_co_u32_e32 v72, vcc, 0x58000, v172
	s_nop 1
	v_addc_co_u32_e32 v73, vcc, 0, v173, vcc
	v_add_co_u32_e32 v76, vcc, 0x84000, v172
	global_load_dwordx4 v[68:71], v[68:69], off
	global_load_dwordx4 v[72:75], v[72:73], off
	v_addc_co_u32_e32 v77, vcc, 0, v173, vcc
	v_add_co_u32_e32 v84, vcc, 0x2c000, v170
	global_load_dwordx4 v[76:79], v[76:77], off
	s_nop 0
	global_load_dwordx4 v[80:83], v[170:171], off
	v_addc_co_u32_e32 v85, vcc, 0, v171, vcc
	v_add_co_u32_e32 v88, vcc, 0x58000, v170
	s_nop 1
	v_addc_co_u32_e32 v89, vcc, 0, v171, vcc
	v_add_co_u32_e32 v92, vcc, 0x84000, v170
	global_load_dwordx4 v[84:87], v[84:85], off
	s_nop 0
	global_load_dwordx4 v[88:91], v[88:89], off
	v_addc_co_u32_e32 v93, vcc, 0, v171, vcc
	global_load_dwordx4 v[92:95], v[92:93], off
.LBB0_1418:
	s_waitcnt lgkmcnt(0)
	s_barrier
	s_setprio 1
	ds_read_b128 v[212:215], v96 offset:36864
	ds_read_b128 v[216:219], v210
	ds_read_b128 v[220:223], v210 offset:4608
	ds_read_b128 v[224:227], v96 offset:41472
	ds_read_b128 v[228:231], v96 offset:36896
	ds_read_b128 v[244:247], v210 offset:32
	ds_read_b128 v[252:255], v210 offset:4640
	s_waitcnt lgkmcnt(5)
	v_mfma_f32_32x32x16_bf16 v[48:63], v[212:215], v[216:219], v[48:63]
	s_waitcnt lgkmcnt(4)
	v_mfma_f32_32x32x16_bf16 v[32:47], v[212:215], v[220:223], v[32:47]
	ds_read_b128 v[212:215], v96 offset:41504
	s_waitcnt lgkmcnt(4)
	v_mfma_f32_32x32x16_bf16 v[16:31], v[224:227], v[216:219], v[16:31]
	ds_read_b128 v[216:219], v96 offset:36928
	v_mfma_f32_32x32x16_bf16 v[0:15], v[224:227], v[220:223], v[0:15]
	ds_read_b128 v[224:227], v210 offset:64
	ds_read_b128 v[220:223], v210 offset:4672
	s_waitcnt lgkmcnt(5)
	v_mfma_f32_32x32x16_bf16 v[48:63], v[228:231], v[244:247], v[48:63]
	s_waitcnt lgkmcnt(4)
	v_mfma_f32_32x32x16_bf16 v[32:47], v[228:231], v[252:255], v[32:47]
	ds_read_b128 v[228:231], v96 offset:41536
	s_waitcnt lgkmcnt(4)
	v_mfma_f32_32x32x16_bf16 v[16:31], v[212:215], v[244:247], v[16:31]
	ds_read_b128 v[244:247], v96 offset:36960
	v_mfma_f32_32x32x16_bf16 v[0:15], v[212:215], v[252:255], v[0:15]
	ds_read_b128 v[212:215], v210 offset:96
	ds_read_b128 v[252:255], v210 offset:4704
	s_waitcnt lgkmcnt(5)
	v_mfma_f32_32x32x16_bf16 v[48:63], v[216:219], v[224:227], v[48:63]
	s_waitcnt lgkmcnt(4)
	v_mfma_f32_32x32x16_bf16 v[32:47], v[216:219], v[220:223], v[32:47]
	ds_read_b128 v[216:219], v96 offset:41568
	s_waitcnt lgkmcnt(4)
	v_mfma_f32_32x32x16_bf16 v[16:31], v[228:231], v[224:227], v[16:31]
	v_mfma_f32_32x32x16_bf16 v[0:15], v[228:231], v[220:223], v[0:15]
	s_waitcnt lgkmcnt(2)
	v_mfma_f32_32x32x16_bf16 v[48:63], v[244:247], v[212:215], v[48:63]
	s_waitcnt lgkmcnt(1)
	v_mfma_f32_32x32x16_bf16 v[32:47], v[244:247], v[252:255], v[32:47]
	s_waitcnt lgkmcnt(0)
	v_mfma_f32_32x32x16_bf16 v[16:31], v[216:219], v[212:215], v[16:31]
	v_mfma_f32_32x32x16_bf16 v[0:15], v[216:219], v[252:255], v[0:15]
	s_setprio 0
	s_and_b64 vcc, exec, s[38:39]
	s_waitcnt vmcnt(7)
	ds_write_b128 v209, v[100:103] offset:18432
	s_waitcnt vmcnt(6)
	ds_write_b128 v209, v[104:107] offset:23040
	s_waitcnt vmcnt(5)
	ds_write_b128 v209, v[108:111] offset:27648
	s_waitcnt vmcnt(4)
	ds_write_b128 v209, v[116:119] offset:32256
	s_waitcnt vmcnt(3)
	ds_write_b128 v209, v[112:115] offset:55296
	s_waitcnt vmcnt(2)
	ds_write_b128 v209, v[120:123] offset:59904
	s_waitcnt vmcnt(1)
	ds_write_b128 v209, v[124:127] offset:64512
	s_waitcnt vmcnt(0)
	ds_write_b128 v211, v[128:131] offset:13824
	s_cbranch_vccnz .LBB0_1420
	v_add_co_u32_e32 v98, vcc, 0x2c000, v172
	global_load_dwordx4 v[100:103], v[172:173], off offset:128
	s_nop 0
	v_addc_co_u32_e32 v99, vcc, 0, v173, vcc
	v_add_co_u32_e32 v108, vcc, 0x58000, v172
	s_nop 1
	v_addc_co_u32_e32 v109, vcc, 0, v173, vcc
	global_load_dwordx4 v[104:107], v[98:99], off offset:128
	global_load_dwordx4 v[108:111], v[108:109], off offset:128
	v_add_co_u32_e32 v98, vcc, 0x84000, v172
	s_nop 1
	v_addc_co_u32_e32 v99, vcc, 0, v173, vcc
	global_load_dwordx4 v[116:119], v[98:99], off offset:128
	global_load_dwordx4 v[112:115], v[170:171], off offset:128
	v_add_co_u32_e32 v98, vcc, 0x2c000, v170
	s_nop 1
	v_addc_co_u32_e32 v99, vcc, 0, v171, vcc
	v_add_co_u32_e32 v124, vcc, 0x58000, v170
	s_nop 1
	v_addc_co_u32_e32 v125, vcc, 0, v171, vcc
	global_load_dwordx4 v[120:123], v[98:99], off offset:128
	s_nop 0
	global_load_dwordx4 v[124:127], v[124:125], off offset:128
	v_add_co_u32_e32 v98, vcc, 0x84000, v170
	s_nop 1
	v_addc_co_u32_e32 v99, vcc, 0, v171, vcc
	global_load_dwordx4 v[128:131], v[98:99], off offset:128
.LBB0_1420:
	s_waitcnt lgkmcnt(0)
	s_barrier
	s_setprio 1
	ds_read_b128 v[212:215], v96 offset:55296
	ds_read_b128 v[216:219], v210 offset:18432
	ds_read_b128 v[220:223], v210 offset:23040
	ds_read_b128 v[224:227], v96 offset:59904
	ds_read_b128 v[228:231], v96 offset:55328
	ds_read_b128 v[244:247], v210 offset:18464
	ds_read_b128 v[252:255], v210 offset:23072
	s_waitcnt lgkmcnt(5)
	v_mfma_f32_32x32x16_bf16 v[48:63], v[212:215], v[216:219], v[48:63]
	s_waitcnt lgkmcnt(4)
	v_mfma_f32_32x32x16_bf16 v[32:47], v[212:215], v[220:223], v[32:47]
	ds_read_b128 v[212:215], v96 offset:59936
	s_waitcnt lgkmcnt(4)
	v_mfma_f32_32x32x16_bf16 v[16:31], v[224:227], v[216:219], v[16:31]
	ds_read_b128 v[216:219], v96 offset:55360
	v_mfma_f32_32x32x16_bf16 v[0:15], v[224:227], v[220:223], v[0:15]
	ds_read_b128 v[224:227], v210 offset:18496
	ds_read_b128 v[220:223], v210 offset:23104
	s_waitcnt lgkmcnt(5)
	v_mfma_f32_32x32x16_bf16 v[48:63], v[228:231], v[244:247], v[48:63]
	s_waitcnt lgkmcnt(4)
	v_mfma_f32_32x32x16_bf16 v[32:47], v[228:231], v[252:255], v[32:47]
	ds_read_b128 v[228:231], v96 offset:59968
	s_waitcnt lgkmcnt(4)
	v_mfma_f32_32x32x16_bf16 v[16:31], v[212:215], v[244:247], v[16:31]
	ds_read_b128 v[244:247], v96 offset:55392
	v_mfma_f32_32x32x16_bf16 v[0:15], v[212:215], v[252:255], v[0:15]
	ds_read_b128 v[212:215], v210 offset:18528
	ds_read_b128 v[252:255], v210 offset:23136
	s_waitcnt lgkmcnt(5)
	v_mfma_f32_32x32x16_bf16 v[48:63], v[216:219], v[224:227], v[48:63]
	s_waitcnt lgkmcnt(4)
	v_mfma_f32_32x32x16_bf16 v[32:47], v[216:219], v[220:223], v[32:47]
	ds_read_b128 v[216:219], v96 offset:60000
	s_waitcnt lgkmcnt(4)
	v_mfma_f32_32x32x16_bf16 v[16:31], v[228:231], v[224:227], v[16:31]
	v_mfma_f32_32x32x16_bf16 v[0:15], v[228:231], v[220:223], v[0:15]
	s_waitcnt lgkmcnt(2)
	v_mfma_f32_32x32x16_bf16 v[48:63], v[244:247], v[212:215], v[48:63]
	s_waitcnt lgkmcnt(1)
	v_mfma_f32_32x32x16_bf16 v[32:47], v[244:247], v[252:255], v[32:47]
	s_waitcnt lgkmcnt(0)
	v_mfma_f32_32x32x16_bf16 v[16:31], v[216:219], v[212:215], v[16:31]
	v_mfma_f32_32x32x16_bf16 v[0:15], v[216:219], v[252:255], v[0:15]
	s_setprio 0
	s_and_b64 vcc, exec, s[38:39]
	s_cbranch_vccnz .LBB0_1422
	ds_write_b128 v209, v[64:67]
	ds_write_b128 v209, v[68:71] offset:4608
	ds_write_b128 v209, v[72:75] offset:9216
	ds_write_b128 v209, v[76:79] offset:13824
	ds_write_b128 v209, v[80:83] offset:36864
	ds_write_b128 v209, v[84:87] offset:41472
	ds_write_b128 v209, v[88:91] offset:46080
	ds_write_b128 v209, v[92:95] offset:50688
	v_add_co_u32_e32 v68, vcc, 0x2c000, v172
	global_load_dwordx4 v[64:67], v[172:173], off offset:256
	s_nop 0
	v_addc_co_u32_e32 v69, vcc, 0, v173, vcc
	v_add_co_u32_e32 v72, vcc, 0x58000, v172
	s_nop 1
	v_addc_co_u32_e32 v73, vcc, 0, v173, vcc
	v_add_co_u32_e32 v76, vcc, 0x84000, v172
	global_load_dwordx4 v[68:71], v[68:69], off offset:256
	s_nop 0
	global_load_dwordx4 v[72:75], v[72:73], off offset:256
	v_addc_co_u32_e32 v77, vcc, 0, v173, vcc
	v_add_co_u32_e32 v84, vcc, 0x2c000, v170
	global_load_dwordx4 v[76:79], v[76:77], off offset:256
	global_load_dwordx4 v[80:83], v[170:171], off offset:256
	v_addc_co_u32_e32 v85, vcc, 0, v171, vcc
	v_add_co_u32_e32 v88, vcc, 0x58000, v170
	s_nop 1
	v_addc_co_u32_e32 v89, vcc, 0, v171, vcc
	v_add_co_u32_e32 v92, vcc, 0x84000, v170
	global_load_dwordx4 v[84:87], v[84:85], off offset:256
	global_load_dwordx4 v[88:91], v[88:89], off offset:256
	v_addc_co_u32_e32 v93, vcc, 0, v171, vcc
	global_load_dwordx4 v[92:95], v[92:93], off offset:256
